# v71 plus write-through (sc1) tile stores in the big-GEMM epilogues, so the XCD L2 holds little dirty data when the grid barrier's write-back runs
# baseline (speedup 1.0000x reference)
; __device__ __forceinline__ unsigned cvt_pk_bf16(float lo, float hi) { unsigned r; asm volatile("v_cvt_pk_bf16_f32 %0, %1, %2" : "=v"(r) : "v"(lo), "v"(hi)); return r; }
; __device__ __forceinline__ f32x2 gelu_pk(f32x2 v) {
;     f32x2 x = v * 0.70710678118f;
;     x.x = __builtin_amdgcn_fmed3f(x.x, -2.9f, 2.9f); x.y = __builtin_amdgcn_fmed3f(x.y, -2.9f, 2.9f);
;     const f32x2 t = x * x;
;     f32x2 p = t * (-4.953124630e-07f) + 1.987094038e-05f;
;     p = p * t + (-3.472001117e-04f); p = p * t + 3.517547622e-03f; p = p * t + (-2.333305031e-02f); p = p * t + 1.087993085e-01f; p = p * t + (-3.740358949e-01f); p = p * t + 1.128076553e+00f;
;     const f32x2 hv = v * 0.5f;
;     return hv * (x * p) + hv;
; }
;     __device__ __forceinline__ void operator()(const f32x4 (&acc)[2][2][4][2], const Unit& u, int wr, int wc, int fr, int fq) const {
;     ...
;             for (int m = 0; m < 4; ++m) { bf16_t* rowp = O + (size_t)(row0 + ai * HALF + m * 16) * ldc + col0;
;                 const float rs = rsqrtf(rsv[ai][m] * (1.f / 1024.f) + 1e-6f);
; #pragma unroll
;                 for (int bj = 0; bj < 2; ++bj) if (bj == 0 || !u.q) { f32x4 v0 = acc[ai][bj][m][0] * rs, v1 = acc[ai][bj][m][1] * rs;
;                     if (act) { f32x2 a = gelu_pk((f32x2){v0[0], v0[1]}), b = gelu_pk((f32x2){v0[2], v0[3]}), c = gelu_pk((f32x2){v1[0], v1[1]}), d = gelu_pk((f32x2){v1[2], v1[3]});
;                         v0 = (f32x4){a.x, a.y, b.x, b.y}; v1 = (f32x4){c.x, c.y, d.x, d.y}; }
;                     u32x4 w; w.x = cvt_pk_bf16(v0[0], v0[1]); w.y = cvt_pk_bf16(v0[2], v0[3]); w.z = cvt_pk_bf16(v1[0], v1[1]); w.w = cvt_pk_bf16(v1[2], v1[3]);
;                     *(u32x4*)(rowp + bj * HALF) = w; } }
.LBB0_99:
	v_readlane_b32 s2, v240, 12
	s_add_i32 s0, s0, s37
	v_readlane_b32 s3, v240, 13
	v_lshl_add_u32 v120, v174, 3, s0
	v_ashrrev_i32_e32 v121, 31, v120
	v_mov_b64_e32 v[122:123], s[2:3]
	v_mad_i64_i32 v[122:123], s[2:3], v158, s91, v[122:123]
	v_lshl_add_u64 v[122:123], v[120:121], 1, v[122:123]
	v_cvt_pk_bf16_f32 v124, v124, v125
	v_cvt_pk_bf16_f32 v125, v126, v127
	v_cvt_pk_bf16_f32 v126, v164, v165
	v_cvt_pk_bf16_f32 v127, v162, v163
	global_store_dwordx4 v[122:123], v[124:127], off sc1
	v_mov_b32_e32 v161, v160
	v_pk_mul_f32 v[116:117], v[116:117], v[160:161]
	v_mov_b32_e32 v124, v160
	v_mov_b32_e32 v125, v160
	v_pk_mul_f32 v[118:119], v[118:119], v[124:125]
	v_pk_mul_f32 v[114:115], v[114:115], v[124:125]
	v_cndmask_b32_e64 v124, 0, 1, s[52:53]
	v_cmp_ne_u32_e64 s[6:7], 1, v124
	s_andn2_b64 vcc, exec, s[52:53]
	v_pk_mul_f32 v[112:113], v[112:113], v[160:161]
	s_cbranch_vccnz .LBB0_101
	v_pk_mul_f32 v[124:125], v[116:117], s[16:17] op_sel_hi:[1,0]
	v_mov_b64_e32 v[158:159], s[20:21]
	v_med3_f32 v124, v124, s90, v173
	v_med3_f32 v125, v125, s90, v173
	v_pk_mul_f32 v[126:127], v[124:125], v[124:125]
	v_pk_mul_f32 v[116:117], v[116:117], 0.5 op_sel_hi:[1,0]
	v_pk_fma_f32 v[160:161], v[126:127], s[18:19], v[158:159] op_sel_hi:[1,0,0] neg_lo:[1,0,0] neg_hi:[1,0,0]
	s_nop 0
	v_pk_fma_f32 v[160:161], v[126:127], v[160:161], s[28:29] op_sel_hi:[1,1,0]
	s_nop 0
	v_pk_fma_f32 v[160:161], v[126:127], v[160:161], s[30:31] op_sel_hi:[1,1,0]
	s_nop 0
	v_pk_fma_f32 v[160:161], v[126:127], v[160:161], s[34:35] op_sel_hi:[1,1,0]
	s_nop 0
	v_pk_fma_f32 v[160:161], v[126:127], v[160:161], s[36:37] op_sel_hi:[1,1,0]
	s_nop 0
	v_pk_fma_f32 v[160:161], v[126:127], v[160:161], s[38:39] op_sel_hi:[1,1,0]
	s_nop 0
	v_pk_fma_f32 v[126:127], v[126:127], v[160:161], s[40:41] op_sel_hi:[1,1,0]
	s_nop 0
	v_pk_mul_f32 v[124:125], v[124:125], v[126:127]
	s_nop 0
	v_pk_fma_f32 v[116:117], v[116:117], v[124:125], v[116:117]
	v_pk_mul_f32 v[124:125], v[118:119], s[16:17] op_sel_hi:[1,0]
	v_pk_mul_f32 v[118:119], v[118:119], 0.5 op_sel_hi:[1,0]
	v_med3_f32 v124, v124, s90, v173
	v_med3_f32 v125, v125, s90, v173
	v_pk_mul_f32 v[126:127], v[124:125], v[124:125]
	s_nop 0
	v_pk_fma_f32 v[160:161], v[126:127], s[18:19], v[158:159] op_sel_hi:[1,0,0] neg_lo:[1,0,0] neg_hi:[1,0,0]
	s_nop 0
	v_pk_fma_f32 v[160:161], v[126:127], v[160:161], s[28:29] op_sel_hi:[1,1,0]
	s_nop 0
	v_pk_fma_f32 v[160:161], v[126:127], v[160:161], s[30:31] op_sel_hi:[1,1,0]
	s_nop 0
	v_pk_fma_f32 v[160:161], v[126:127], v[160:161], s[34:35] op_sel_hi:[1,1,0]
	s_nop 0
	v_pk_fma_f32 v[160:161], v[126:127], v[160:161], s[36:37] op_sel_hi:[1,1,0]
	s_nop 0
	v_pk_fma_f32 v[160:161], v[126:127], v[160:161], s[38:39] op_sel_hi:[1,1,0]
	s_nop 0
	v_pk_fma_f32 v[126:127], v[126:127], v[160:161], s[40:41] op_sel_hi:[1,1,0]
	s_nop 0
	v_pk_mul_f32 v[124:125], v[124:125], v[126:127]
	s_nop 0
	v_pk_fma_f32 v[118:119], v[118:119], v[124:125], v[118:119]
	v_pk_mul_f32 v[124:125], v[112:113], s[16:17] op_sel_hi:[1,0]
	v_pk_mul_f32 v[112:113], v[112:113], 0.5 op_sel_hi:[1,0]
	v_med3_f32 v124, v124, s90, v173
	v_med3_f32 v125, v125, s90, v173
	v_pk_mul_f32 v[126:127], v[124:125], v[124:125]
	s_nop 0
	v_pk_fma_f32 v[160:161], v[126:127], s[18:19], v[158:159] op_sel_hi:[1,0,0] neg_lo:[1,0,0] neg_hi:[1,0,0]
	s_nop 0
	v_pk_fma_f32 v[160:161], v[126:127], v[160:161], s[28:29] op_sel_hi:[1,1,0]
	s_nop 0
	v_pk_fma_f32 v[160:161], v[126:127], v[160:161], s[30:31] op_sel_hi:[1,1,0]
	s_nop 0
	v_pk_fma_f32 v[160:161], v[126:127], v[160:161], s[34:35] op_sel_hi:[1,1,0]
	s_nop 0
	v_pk_fma_f32 v[160:161], v[126:127], v[160:161], s[36:37] op_sel_hi:[1,1,0]
	s_nop 0
	v_pk_fma_f32 v[160:161], v[126:127], v[160:161], s[38:39] op_sel_hi:[1,1,0]
	s_nop 0
	v_pk_fma_f32 v[126:127], v[126:127], v[160:161], s[40:41] op_sel_hi:[1,1,0]
	s_nop 0
	v_pk_mul_f32 v[124:125], v[124:125], v[126:127]
	s_nop 0
	v_pk_fma_f32 v[112:113], v[112:113], v[124:125], v[112:113]
	v_pk_mul_f32 v[124:125], v[114:115], s[16:17] op_sel_hi:[1,0]
	v_pk_mul_f32 v[114:115], v[114:115], 0.5 op_sel_hi:[1,0]
	v_med3_f32 v124, v124, s90, v173
	v_med3_f32 v125, v125, s90, v173
	v_pk_mul_f32 v[126:127], v[124:125], v[124:125]
	s_nop 0
	v_pk_fma_f32 v[158:159], v[126:127], s[18:19], v[158:159] op_sel_hi:[1,0,0] neg_lo:[1,0,0] neg_hi:[1,0,0]
	s_nop 0
	v_pk_fma_f32 v[158:159], v[126:127], v[158:159], s[28:29] op_sel_hi:[1,1,0]
	s_nop 0
	v_pk_fma_f32 v[158:159], v[126:127], v[158:159], s[30:31] op_sel_hi:[1,1,0]
	s_nop 0
	v_pk_fma_f32 v[158:159], v[126:127], v[158:159], s[34:35] op_sel_hi:[1,1,0]
	s_nop 0
	v_pk_fma_f32 v[158:159], v[126:127], v[158:159], s[36:37] op_sel_hi:[1,1,0]
	s_nop 0
	v_pk_fma_f32 v[158:159], v[126:127], v[158:159], s[38:39] op_sel_hi:[1,1,0]
	s_nop 0
	v_pk_fma_f32 v[126:127], v[126:127], v[158:159], s[40:41] op_sel_hi:[1,1,0]
	s_nop 0
	v_pk_mul_f32 v[124:125], v[124:125], v[126:127]
	s_nop 0
	v_pk_fma_f32 v[114:115], v[114:115], v[124:125], v[114:115]
; __device__ __forceinline__ unsigned cvt_pk_bf16(float lo, float hi) { unsigned r; asm volatile("v_cvt_pk_bf16_f32 %0, %1, %2" : "=v"(r) : "v"(lo), "v"(hi)); return r; }
; __device__ __forceinline__ f32x2 gelu_pk(f32x2 v) {
;     f32x2 x = v * 0.70710678118f;
;     x.x = __builtin_amdgcn_fmed3f(x.x, -2.9f, 2.9f); x.y = __builtin_amdgcn_fmed3f(x.y, -2.9f, 2.9f);
;     const f32x2 t = x * x;
;     f32x2 p = t * (-4.953124630e-07f) + 1.987094038e-05f;
;     p = p * t + (-3.472001117e-04f); p = p * t + 3.517547622e-03f; p = p * t + (-2.333305031e-02f); p = p * t + 1.087993085e-01f; p = p * t + (-3.740358949e-01f); p = p * t + 1.128076553e+00f;
;     const f32x2 hv = v * 0.5f;
;     return hv * (x * p) + hv;
; }
;     __device__ __forceinline__ void operator()(const f32x4 (&acc)[2][2][4][2], const Unit& u, int wr, int wc, int fr, int fq) const {
;     ...
;             for (int m = 0; m < 4; ++m) { bf16_t* rowp = O + (size_t)(row0 + ai * HALF + m * 16) * ldc + col0;
;                 const float rs = rsqrtf(rsv[ai][m] * (1.f / 1024.f) + 1e-6f);
; #pragma unroll
;                 for (int bj = 0; bj < 2; ++bj) if (bj == 0 || !u.q) { f32x4 v0 = acc[ai][bj][m][0] * rs, v1 = acc[ai][bj][m][1] * rs;
;                     if (act) { f32x2 a = gelu_pk((f32x2){v0[0], v0[1]}), b = gelu_pk((f32x2){v0[2], v0[3]}), c = gelu_pk((f32x2){v1[0], v1[1]}), d = gelu_pk((f32x2){v1[2], v1[3]});
;                         v0 = (f32x4){a.x, a.y, b.x, b.y}; v1 = (f32x4){c.x, c.y, d.x, d.y}; }
;                     u32x4 w; w.x = cvt_pk_bf16(v0[0], v0[1]); w.y = cvt_pk_bf16(v0[2], v0[3]); w.z = cvt_pk_bf16(v1[0], v1[1]); w.w = cvt_pk_bf16(v1[2], v1[3]);
;                     *(u32x4*)(rowp + bj * HALF) = w; } }
.LBB0_101:
	v_cvt_pk_bf16_f32 v116, v116, v117
	v_cvt_pk_bf16_f32 v117, v118, v119
	v_fmamk_f32 v118, v157, 0x3a800000, v172
	v_mul_f32_e32 v119, 0x4b800000, v118
	v_cmp_gt_f32_e32 vcc, s87, v118
	s_nop 1
	v_cndmask_b32_e32 v118, v118, v119, vcc
	v_rsq_f32_e32 v124, v118
	v_cvt_pk_bf16_f32 v118, v112, v113
	v_cvt_pk_bf16_f32 v119, v114, v115
	global_store_dwordx4 v[122:123], v[116:119], off offset:256 sc1
	v_mul_f32_e32 v112, 0x45800000, v124
	v_cndmask_b32_e32 v112, v124, v112, vcc
	v_pk_mul_f32 v[110:111], v[110:111], v[112:113] op_sel_hi:[1,0]
	v_pk_mul_f32 v[108:109], v[108:109], v[112:113] op_sel_hi:[1,0]
	v_pk_mul_f32 v[106:107], v[106:107], v[112:113] op_sel_hi:[1,0]
	s_and_b64 vcc, exec, s[6:7]
	v_pk_mul_f32 v[114:115], v[104:105], v[112:113] op_sel_hi:[1,0]
	s_cbranch_vccnz .LBB0_103
	v_pk_mul_f32 v[104:105], v[108:109], s[16:17] op_sel_hi:[1,0]
	v_mov_b64_e32 v[118:119], s[20:21]
	v_med3_f32 v104, v104, s90, v173
	v_med3_f32 v105, v105, s90, v173
	v_pk_mul_f32 v[116:117], v[104:105], v[104:105]
	v_pk_mul_f32 v[108:109], v[108:109], 0.5 op_sel_hi:[1,0]
	v_pk_fma_f32 v[122:123], v[116:117], s[18:19], v[118:119] op_sel_hi:[1,0,0] neg_lo:[1,0,0] neg_hi:[1,0,0]
	s_nop 0
	v_pk_fma_f32 v[122:123], v[116:117], v[122:123], s[28:29] op_sel_hi:[1,1,0]
	s_nop 0
	v_pk_fma_f32 v[122:123], v[116:117], v[122:123], s[30:31] op_sel_hi:[1,1,0]
	s_nop 0
	v_pk_fma_f32 v[122:123], v[116:117], v[122:123], s[34:35] op_sel_hi:[1,1,0]
	s_nop 0
	v_pk_fma_f32 v[122:123], v[116:117], v[122:123], s[36:37] op_sel_hi:[1,1,0]
	s_nop 0
	v_pk_fma_f32 v[122:123], v[116:117], v[122:123], s[38:39] op_sel_hi:[1,1,0]
	s_nop 0
	v_pk_fma_f32 v[116:117], v[116:117], v[122:123], s[40:41] op_sel_hi:[1,1,0]
	s_nop 0
	v_pk_mul_f32 v[104:105], v[104:105], v[116:117]
	s_nop 0
	v_pk_fma_f32 v[108:109], v[108:109], v[104:105], v[108:109]
	v_pk_mul_f32 v[104:105], v[110:111], s[16:17] op_sel_hi:[1,0]
	v_pk_mul_f32 v[110:111], v[110:111], 0.5 op_sel_hi:[1,0]
	v_med3_f32 v104, v104, s90, v173
	v_med3_f32 v105, v105, s90, v173
	v_pk_mul_f32 v[116:117], v[104:105], v[104:105]
	s_nop 0
	v_pk_fma_f32 v[122:123], v[116:117], s[18:19], v[118:119] op_sel_hi:[1,0,0] neg_lo:[1,0,0] neg_hi:[1,0,0]
	s_nop 0
	v_pk_fma_f32 v[122:123], v[116:117], v[122:123], s[28:29] op_sel_hi:[1,1,0]
	s_nop 0
	v_pk_fma_f32 v[122:123], v[116:117], v[122:123], s[30:31] op_sel_hi:[1,1,0]
	s_nop 0
	v_pk_fma_f32 v[122:123], v[116:117], v[122:123], s[34:35] op_sel_hi:[1,1,0]
	s_nop 0
	v_pk_fma_f32 v[122:123], v[116:117], v[122:123], s[36:37] op_sel_hi:[1,1,0]
	s_nop 0
	v_pk_fma_f32 v[122:123], v[116:117], v[122:123], s[38:39] op_sel_hi:[1,1,0]
	s_nop 0
	v_pk_fma_f32 v[116:117], v[116:117], v[122:123], s[40:41] op_sel_hi:[1,1,0]
	s_nop 0
	v_pk_mul_f32 v[104:105], v[104:105], v[116:117]
	s_nop 0
	v_pk_fma_f32 v[110:111], v[110:111], v[104:105], v[110:111]
	v_pk_mul_f32 v[104:105], v[114:115], s[16:17] op_sel_hi:[1,0]
	v_pk_mul_f32 v[114:115], v[114:115], 0.5 op_sel_hi:[1,0]
	v_med3_f32 v104, v104, s90, v173
	v_med3_f32 v105, v105, s90, v173
	v_pk_mul_f32 v[116:117], v[104:105], v[104:105]
	s_nop 0
	v_pk_fma_f32 v[122:123], v[116:117], s[18:19], v[118:119] op_sel_hi:[1,0,0] neg_lo:[1,0,0] neg_hi:[1,0,0]
	s_nop 0
	v_pk_fma_f32 v[122:123], v[116:117], v[122:123], s[28:29] op_sel_hi:[1,1,0]
	s_nop 0
	v_pk_fma_f32 v[122:123], v[116:117], v[122:123], s[30:31] op_sel_hi:[1,1,0]
	s_nop 0
	v_pk_fma_f32 v[122:123], v[116:117], v[122:123], s[34:35] op_sel_hi:[1,1,0]
	s_nop 0
	v_pk_fma_f32 v[122:123], v[116:117], v[122:123], s[36:37] op_sel_hi:[1,1,0]
	s_nop 0
	v_pk_fma_f32 v[122:123], v[116:117], v[122:123], s[38:39] op_sel_hi:[1,1,0]
	s_nop 0
	v_pk_fma_f32 v[116:117], v[116:117], v[122:123], s[40:41] op_sel_hi:[1,1,0]
	s_nop 0
	v_pk_mul_f32 v[104:105], v[104:105], v[116:117]
	s_nop 0
	v_pk_fma_f32 v[114:115], v[114:115], v[104:105], v[114:115]
	v_pk_mul_f32 v[104:105], v[106:107], s[16:17] op_sel_hi:[1,0]
	v_pk_mul_f32 v[106:107], v[106:107], 0.5 op_sel_hi:[1,0]
	v_med3_f32 v104, v104, s90, v173
	v_med3_f32 v105, v105, s90, v173
	v_pk_mul_f32 v[116:117], v[104:105], v[104:105]
	s_nop 0
	v_pk_fma_f32 v[118:119], v[116:117], s[18:19], v[118:119] op_sel_hi:[1,0,0] neg_lo:[1,0,0] neg_hi:[1,0,0]
	s_nop 0
	v_pk_fma_f32 v[118:119], v[116:117], v[118:119], s[28:29] op_sel_hi:[1,1,0]
	s_nop 0
	v_pk_fma_f32 v[118:119], v[116:117], v[118:119], s[30:31] op_sel_hi:[1,1,0]
	s_nop 0
	v_pk_fma_f32 v[118:119], v[116:117], v[118:119], s[34:35] op_sel_hi:[1,1,0]
	s_nop 0
	v_pk_fma_f32 v[118:119], v[116:117], v[118:119], s[36:37] op_sel_hi:[1,1,0]
	s_nop 0
	v_pk_fma_f32 v[118:119], v[116:117], v[118:119], s[38:39] op_sel_hi:[1,1,0]
	s_nop 0
	v_pk_fma_f32 v[116:117], v[116:117], v[118:119], s[40:41] op_sel_hi:[1,1,0]
	s_nop 0
	v_pk_mul_f32 v[104:105], v[104:105], v[116:117]
	s_nop 0
	v_pk_fma_f32 v[106:107], v[106:107], v[104:105], v[106:107]
; __device__ __forceinline__ unsigned cvt_pk_bf16(float lo, float hi) { unsigned r; asm volatile("v_cvt_pk_bf16_f32 %0, %1, %2" : "=v"(r) : "v"(lo), "v"(hi)); return r; }
; __device__ __forceinline__ f32x2 gelu_pk(f32x2 v) {
;     f32x2 x = v * 0.70710678118f;
;     x.x = __builtin_amdgcn_fmed3f(x.x, -2.9f, 2.9f); x.y = __builtin_amdgcn_fmed3f(x.y, -2.9f, 2.9f);
;     const f32x2 t = x * x;
;     f32x2 p = t * (-4.953124630e-07f) + 1.987094038e-05f;
;     p = p * t + (-3.472001117e-04f); p = p * t + 3.517547622e-03f; p = p * t + (-2.333305031e-02f); p = p * t + 1.087993085e-01f; p = p * t + (-3.740358949e-01f); p = p * t + 1.128076553e+00f;
;     const f32x2 hv = v * 0.5f;
;     return hv * (x * p) + hv;
; }
;     __device__ __forceinline__ void operator()(const f32x4 (&acc)[2][2][4][2], const Unit& u, int wr, int wc, int fr, int fq) const {
;     ...
;             for (int m = 0; m < 4; ++m) { bf16_t* rowp = O + (size_t)(row0 + ai * HALF + m * 16) * ldc + col0;
;                 const float rs = rsqrtf(rsv[ai][m] * (1.f / 1024.f) + 1e-6f);
; #pragma unroll
;                 for (int bj = 0; bj < 2; ++bj) if (bj == 0 || !u.q) { f32x4 v0 = acc[ai][bj][m][0] * rs, v1 = acc[ai][bj][m][1] * rs;
;                     if (act) { f32x2 a = gelu_pk((f32x2){v0[0], v0[1]}), b = gelu_pk((f32x2){v0[2], v0[3]}), c = gelu_pk((f32x2){v1[0], v1[1]}), d = gelu_pk((f32x2){v1[2], v1[3]});
;                         v0 = (f32x4){a.x, a.y, b.x, b.y}; v1 = (f32x4){c.x, c.y, d.x, d.y}; }
;                     u32x4 w; w.x = cvt_pk_bf16(v0[0], v0[1]); w.y = cvt_pk_bf16(v0[2], v0[3]); w.z = cvt_pk_bf16(v1[0], v1[1]); w.w = cvt_pk_bf16(v1[2], v1[3]);
;                     *(u32x4*)(rowp + bj * HALF) = w; } }
.LBB0_103:
	v_readlane_b32 s2, v240, 12
	v_readlane_b32 s3, v240, 13
	v_mov_b32_e32 v113, v112
	v_cvt_pk_bf16_f32 v108, v108, v109
	v_cvt_pk_bf16_f32 v109, v110, v111
	v_cvt_pk_bf16_f32 v110, v114, v115
	v_cvt_pk_bf16_f32 v111, v106, v107
	s_nop 0
	v_mov_b64_e32 v[104:105], s[2:3]
	v_mad_i64_i32 v[104:105], s[2:3], v156, s91, v[104:105]
	v_mov_b32_e32 v106, v112
	v_mov_b32_e32 v107, v112
	v_lshl_add_u64 v[104:105], v[120:121], 1, v[104:105]
	v_pk_mul_f32 v[102:103], v[102:103], v[106:107]
	v_pk_mul_f32 v[100:101], v[100:101], v[112:113]
	v_pk_mul_f32 v[98:99], v[98:99], v[106:107]
	s_and_b64 vcc, exec, s[6:7]
	v_pk_mul_f32 v[96:97], v[96:97], v[112:113]
	global_store_dwordx4 v[104:105], v[108:111], off sc1
	s_cbranch_vccnz .LBB0_105
	v_pk_mul_f32 v[106:107], v[100:101], s[16:17] op_sel_hi:[1,0]
	v_mov_b64_e32 v[110:111], s[20:21]
	v_med3_f32 v106, v106, s90, v173
	v_med3_f32 v107, v107, s90, v173
	v_pk_mul_f32 v[108:109], v[106:107], v[106:107]
	v_pk_mul_f32 v[100:101], v[100:101], 0.5 op_sel_hi:[1,0]
	v_pk_fma_f32 v[112:113], v[108:109], s[18:19], v[110:111] op_sel_hi:[1,0,0] neg_lo:[1,0,0] neg_hi:[1,0,0]
	s_nop 0
	v_pk_fma_f32 v[112:113], v[108:109], v[112:113], s[28:29] op_sel_hi:[1,1,0]
	s_nop 0
	v_pk_fma_f32 v[112:113], v[108:109], v[112:113], s[30:31] op_sel_hi:[1,1,0]
	s_nop 0
	v_pk_fma_f32 v[112:113], v[108:109], v[112:113], s[34:35] op_sel_hi:[1,1,0]
	s_nop 0
	v_pk_fma_f32 v[112:113], v[108:109], v[112:113], s[36:37] op_sel_hi:[1,1,0]
	s_nop 0
	v_pk_fma_f32 v[112:113], v[108:109], v[112:113], s[38:39] op_sel_hi:[1,1,0]
	s_nop 0
	v_pk_fma_f32 v[108:109], v[108:109], v[112:113], s[40:41] op_sel_hi:[1,1,0]
	s_nop 0
	v_pk_mul_f32 v[106:107], v[106:107], v[108:109]
	s_nop 0
	v_pk_fma_f32 v[100:101], v[100:101], v[106:107], v[100:101]
	v_pk_mul_f32 v[106:107], v[102:103], s[16:17] op_sel_hi:[1,0]
	v_pk_mul_f32 v[102:103], v[102:103], 0.5 op_sel_hi:[1,0]
	v_med3_f32 v106, v106, s90, v173
	v_med3_f32 v107, v107, s90, v173
	v_pk_mul_f32 v[108:109], v[106:107], v[106:107]
	s_nop 0
	v_pk_fma_f32 v[112:113], v[108:109], s[18:19], v[110:111] op_sel_hi:[1,0,0] neg_lo:[1,0,0] neg_hi:[1,0,0]
	s_nop 0
	v_pk_fma_f32 v[112:113], v[108:109], v[112:113], s[28:29] op_sel_hi:[1,1,0]
	s_nop 0
	v_pk_fma_f32 v[112:113], v[108:109], v[112:113], s[30:31] op_sel_hi:[1,1,0]
	s_nop 0
	v_pk_fma_f32 v[112:113], v[108:109], v[112:113], s[34:35] op_sel_hi:[1,1,0]
	s_nop 0
	v_pk_fma_f32 v[112:113], v[108:109], v[112:113], s[36:37] op_sel_hi:[1,1,0]
	s_nop 0
	v_pk_fma_f32 v[112:113], v[108:109], v[112:113], s[38:39] op_sel_hi:[1,1,0]
	s_nop 0
	v_pk_fma_f32 v[108:109], v[108:109], v[112:113], s[40:41] op_sel_hi:[1,1,0]
	s_nop 0
	v_pk_mul_f32 v[106:107], v[106:107], v[108:109]
	s_nop 0
	v_pk_fma_f32 v[102:103], v[102:103], v[106:107], v[102:103]
	v_pk_mul_f32 v[106:107], v[96:97], s[16:17] op_sel_hi:[1,0]
	v_pk_mul_f32 v[96:97], v[96:97], 0.5 op_sel_hi:[1,0]
	v_med3_f32 v106, v106, s90, v173
	v_med3_f32 v107, v107, s90, v173
	v_pk_mul_f32 v[108:109], v[106:107], v[106:107]
	s_nop 0
	v_pk_fma_f32 v[112:113], v[108:109], s[18:19], v[110:111] op_sel_hi:[1,0,0] neg_lo:[1,0,0] neg_hi:[1,0,0]
	s_nop 0
	v_pk_fma_f32 v[112:113], v[108:109], v[112:113], s[28:29] op_sel_hi:[1,1,0]
	s_nop 0
	v_pk_fma_f32 v[112:113], v[108:109], v[112:113], s[30:31] op_sel_hi:[1,1,0]
	s_nop 0
	v_pk_fma_f32 v[112:113], v[108:109], v[112:113], s[34:35] op_sel_hi:[1,1,0]
	s_nop 0
	v_pk_fma_f32 v[112:113], v[108:109], v[112:113], s[36:37] op_sel_hi:[1,1,0]
	s_nop 0
	v_pk_fma_f32 v[112:113], v[108:109], v[112:113], s[38:39] op_sel_hi:[1,1,0]
	s_nop 0
	v_pk_fma_f32 v[108:109], v[108:109], v[112:113], s[40:41] op_sel_hi:[1,1,0]
	s_nop 0
	v_pk_mul_f32 v[106:107], v[106:107], v[108:109]
	s_nop 0
	v_pk_fma_f32 v[96:97], v[96:97], v[106:107], v[96:97]
	v_pk_mul_f32 v[106:107], v[98:99], s[16:17] op_sel_hi:[1,0]
	v_pk_mul_f32 v[98:99], v[98:99], 0.5 op_sel_hi:[1,0]
	v_med3_f32 v106, v106, s90, v173
	v_med3_f32 v107, v107, s90, v173
	v_pk_mul_f32 v[108:109], v[106:107], v[106:107]
	s_nop 0
	v_pk_fma_f32 v[110:111], v[108:109], s[18:19], v[110:111] op_sel_hi:[1,0,0] neg_lo:[1,0,0] neg_hi:[1,0,0]
	s_nop 0
	v_pk_fma_f32 v[110:111], v[108:109], v[110:111], s[28:29] op_sel_hi:[1,1,0]
	s_nop 0
	v_pk_fma_f32 v[110:111], v[108:109], v[110:111], s[30:31] op_sel_hi:[1,1,0]
	s_nop 0
	v_pk_fma_f32 v[110:111], v[108:109], v[110:111], s[34:35] op_sel_hi:[1,1,0]
	s_nop 0
	v_pk_fma_f32 v[110:111], v[108:109], v[110:111], s[36:37] op_sel_hi:[1,1,0]
	s_nop 0
	v_pk_fma_f32 v[110:111], v[108:109], v[110:111], s[38:39] op_sel_hi:[1,1,0]
	s_nop 0
	v_pk_fma_f32 v[108:109], v[108:109], v[110:111], s[40:41] op_sel_hi:[1,1,0]
	s_nop 0
	v_pk_mul_f32 v[106:107], v[106:107], v[108:109]
	s_nop 0
	v_pk_fma_f32 v[98:99], v[98:99], v[106:107], v[98:99]
; __device__ __forceinline__ unsigned cvt_pk_bf16(float lo, float hi) { unsigned r; asm volatile("v_cvt_pk_bf16_f32 %0, %1, %2" : "=v"(r) : "v"(lo), "v"(hi)); return r; }
; __device__ __forceinline__ f32x2 gelu_pk(f32x2 v) {
;     f32x2 x = v * 0.70710678118f;
;     x.x = __builtin_amdgcn_fmed3f(x.x, -2.9f, 2.9f); x.y = __builtin_amdgcn_fmed3f(x.y, -2.9f, 2.9f);
;     const f32x2 t = x * x;
;     f32x2 p = t * (-4.953124630e-07f) + 1.987094038e-05f;
;     p = p * t + (-3.472001117e-04f); p = p * t + 3.517547622e-03f; p = p * t + (-2.333305031e-02f); p = p * t + 1.087993085e-01f; p = p * t + (-3.740358949e-01f); p = p * t + 1.128076553e+00f;
;     const f32x2 hv = v * 0.5f;
;     return hv * (x * p) + hv;
; }
;     __device__ __forceinline__ void operator()(const f32x4 (&acc)[2][2][4][2], const Unit& u, int wr, int wc, int fr, int fq) const {
;     ...
;             for (int m = 0; m < 4; ++m) { bf16_t* rowp = O + (size_t)(row0 + ai * HALF + m * 16) * ldc + col0;
;                 const float rs = rsqrtf(rsv[ai][m] * (1.f / 1024.f) + 1e-6f);
; #pragma unroll
;                 for (int bj = 0; bj < 2; ++bj) if (bj == 0 || !u.q) { f32x4 v0 = acc[ai][bj][m][0] * rs, v1 = acc[ai][bj][m][1] * rs;
;                     if (act) { f32x2 a = gelu_pk((f32x2){v0[0], v0[1]}), b = gelu_pk((f32x2){v0[2], v0[3]}), c = gelu_pk((f32x2){v1[0], v1[1]}), d = gelu_pk((f32x2){v1[2], v1[3]});
;                         v0 = (f32x4){a.x, a.y, b.x, b.y}; v1 = (f32x4){c.x, c.y, d.x, d.y}; }
;                     u32x4 w; w.x = cvt_pk_bf16(v0[0], v0[1]); w.y = cvt_pk_bf16(v0[2], v0[3]); w.z = cvt_pk_bf16(v1[0], v1[1]); w.w = cvt_pk_bf16(v1[2], v1[3]);
;                     *(u32x4*)(rowp + bj * HALF) = w; } }
.LBB0_105:
	v_cvt_pk_bf16_f32 v100, v100, v101
	v_cvt_pk_bf16_f32 v101, v102, v103
	v_fmamk_f32 v102, v155, 0x3a800000, v172
	v_mul_f32_e32 v103, 0x4b800000, v102
	v_cmp_gt_f32_e32 vcc, s87, v102
	s_nop 1
	v_cndmask_b32_e32 v102, v102, v103, vcc
	v_rsq_f32_e32 v106, v102
	v_cvt_pk_bf16_f32 v102, v96, v97
	v_cvt_pk_bf16_f32 v103, v98, v99
	global_store_dwordx4 v[104:105], v[100:103], off offset:256 sc1
	v_mul_f32_e32 v96, 0x45800000, v106
	v_cndmask_b32_e32 v96, v106, v96, vcc
	v_pk_mul_f32 v[94:95], v[94:95], v[96:97] op_sel_hi:[1,0]
	v_pk_mul_f32 v[92:93], v[92:93], v[96:97] op_sel_hi:[1,0]
	v_pk_mul_f32 v[90:91], v[90:91], v[96:97] op_sel_hi:[1,0]
	s_and_b64 vcc, exec, s[6:7]
	v_pk_mul_f32 v[98:99], v[88:89], v[96:97] op_sel_hi:[1,0]
	s_cbranch_vccnz .LBB0_107
	v_pk_mul_f32 v[88:89], v[92:93], s[16:17] op_sel_hi:[1,0]
	v_mov_b64_e32 v[102:103], s[20:21]
	v_med3_f32 v88, v88, s90, v173
	v_med3_f32 v89, v89, s90, v173
	v_pk_mul_f32 v[100:101], v[88:89], v[88:89]
	v_pk_mul_f32 v[92:93], v[92:93], 0.5 op_sel_hi:[1,0]
	v_pk_fma_f32 v[104:105], v[100:101], s[18:19], v[102:103] op_sel_hi:[1,0,0] neg_lo:[1,0,0] neg_hi:[1,0,0]
	s_nop 0
	v_pk_fma_f32 v[104:105], v[100:101], v[104:105], s[28:29] op_sel_hi:[1,1,0]
	s_nop 0
	v_pk_fma_f32 v[104:105], v[100:101], v[104:105], s[30:31] op_sel_hi:[1,1,0]
	s_nop 0
	v_pk_fma_f32 v[104:105], v[100:101], v[104:105], s[34:35] op_sel_hi:[1,1,0]
	s_nop 0
	v_pk_fma_f32 v[104:105], v[100:101], v[104:105], s[36:37] op_sel_hi:[1,1,0]
	s_nop 0
	v_pk_fma_f32 v[104:105], v[100:101], v[104:105], s[38:39] op_sel_hi:[1,1,0]
	s_nop 0
	v_pk_fma_f32 v[100:101], v[100:101], v[104:105], s[40:41] op_sel_hi:[1,1,0]
	s_nop 0
	v_pk_mul_f32 v[88:89], v[88:89], v[100:101]
	s_nop 0
	v_pk_fma_f32 v[92:93], v[92:93], v[88:89], v[92:93]
	v_pk_mul_f32 v[88:89], v[94:95], s[16:17] op_sel_hi:[1,0]
	v_pk_mul_f32 v[94:95], v[94:95], 0.5 op_sel_hi:[1,0]
	v_med3_f32 v88, v88, s90, v173
	v_med3_f32 v89, v89, s90, v173
	v_pk_mul_f32 v[100:101], v[88:89], v[88:89]
	s_nop 0
	v_pk_fma_f32 v[104:105], v[100:101], s[18:19], v[102:103] op_sel_hi:[1,0,0] neg_lo:[1,0,0] neg_hi:[1,0,0]
	s_nop 0
	v_pk_fma_f32 v[104:105], v[100:101], v[104:105], s[28:29] op_sel_hi:[1,1,0]
	s_nop 0
	v_pk_fma_f32 v[104:105], v[100:101], v[104:105], s[30:31] op_sel_hi:[1,1,0]
	s_nop 0
	v_pk_fma_f32 v[104:105], v[100:101], v[104:105], s[34:35] op_sel_hi:[1,1,0]
	s_nop 0
	v_pk_fma_f32 v[104:105], v[100:101], v[104:105], s[36:37] op_sel_hi:[1,1,0]
	s_nop 0
	v_pk_fma_f32 v[104:105], v[100:101], v[104:105], s[38:39] op_sel_hi:[1,1,0]
	s_nop 0
	v_pk_fma_f32 v[100:101], v[100:101], v[104:105], s[40:41] op_sel_hi:[1,1,0]
	s_nop 0
	v_pk_mul_f32 v[88:89], v[88:89], v[100:101]
	s_nop 0
	v_pk_fma_f32 v[94:95], v[94:95], v[88:89], v[94:95]
	v_pk_mul_f32 v[88:89], v[98:99], s[16:17] op_sel_hi:[1,0]
	v_pk_mul_f32 v[98:99], v[98:99], 0.5 op_sel_hi:[1,0]
	v_med3_f32 v88, v88, s90, v173
	v_med3_f32 v89, v89, s90, v173
	v_pk_mul_f32 v[100:101], v[88:89], v[88:89]
	s_nop 0
	v_pk_fma_f32 v[104:105], v[100:101], s[18:19], v[102:103] op_sel_hi:[1,0,0] neg_lo:[1,0,0] neg_hi:[1,0,0]
	s_nop 0
	v_pk_fma_f32 v[104:105], v[100:101], v[104:105], s[28:29] op_sel_hi:[1,1,0]
	s_nop 0
	v_pk_fma_f32 v[104:105], v[100:101], v[104:105], s[30:31] op_sel_hi:[1,1,0]
	s_nop 0
	v_pk_fma_f32 v[104:105], v[100:101], v[104:105], s[34:35] op_sel_hi:[1,1,0]
	s_nop 0
	v_pk_fma_f32 v[104:105], v[100:101], v[104:105], s[36:37] op_sel_hi:[1,1,0]
	s_nop 0
	v_pk_fma_f32 v[104:105], v[100:101], v[104:105], s[38:39] op_sel_hi:[1,1,0]
	s_nop 0
	v_pk_fma_f32 v[100:101], v[100:101], v[104:105], s[40:41] op_sel_hi:[1,1,0]
	s_nop 0
	v_pk_mul_f32 v[88:89], v[88:89], v[100:101]
	s_nop 0
	v_pk_fma_f32 v[98:99], v[98:99], v[88:89], v[98:99]
	v_pk_mul_f32 v[88:89], v[90:91], s[16:17] op_sel_hi:[1,0]
	v_pk_mul_f32 v[90:91], v[90:91], 0.5 op_sel_hi:[1,0]
	v_med3_f32 v88, v88, s90, v173
	v_med3_f32 v89, v89, s90, v173
	v_pk_mul_f32 v[100:101], v[88:89], v[88:89]
	s_nop 0
	v_pk_fma_f32 v[102:103], v[100:101], s[18:19], v[102:103] op_sel_hi:[1,0,0] neg_lo:[1,0,0] neg_hi:[1,0,0]
	s_nop 0
	v_pk_fma_f32 v[102:103], v[100:101], v[102:103], s[28:29] op_sel_hi:[1,1,0]
	s_nop 0
	v_pk_fma_f32 v[102:103], v[100:101], v[102:103], s[30:31] op_sel_hi:[1,1,0]
	s_nop 0
	v_pk_fma_f32 v[102:103], v[100:101], v[102:103], s[34:35] op_sel_hi:[1,1,0]
	s_nop 0
	v_pk_fma_f32 v[102:103], v[100:101], v[102:103], s[36:37] op_sel_hi:[1,1,0]
	s_nop 0
	v_pk_fma_f32 v[102:103], v[100:101], v[102:103], s[38:39] op_sel_hi:[1,1,0]
	s_nop 0
	v_pk_fma_f32 v[100:101], v[100:101], v[102:103], s[40:41] op_sel_hi:[1,1,0]
	s_nop 0
	v_pk_mul_f32 v[88:89], v[88:89], v[100:101]
	s_nop 0
	v_pk_fma_f32 v[90:91], v[90:91], v[88:89], v[90:91]
; __device__ __forceinline__ unsigned cvt_pk_bf16(float lo, float hi) { unsigned r; asm volatile("v_cvt_pk_bf16_f32 %0, %1, %2" : "=v"(r) : "v"(lo), "v"(hi)); return r; }
; __device__ __forceinline__ f32x2 gelu_pk(f32x2 v) {
;     f32x2 x = v * 0.70710678118f;
;     x.x = __builtin_amdgcn_fmed3f(x.x, -2.9f, 2.9f); x.y = __builtin_amdgcn_fmed3f(x.y, -2.9f, 2.9f);
;     const f32x2 t = x * x;
;     f32x2 p = t * (-4.953124630e-07f) + 1.987094038e-05f;
;     p = p * t + (-3.472001117e-04f); p = p * t + 3.517547622e-03f; p = p * t + (-2.333305031e-02f); p = p * t + 1.087993085e-01f; p = p * t + (-3.740358949e-01f); p = p * t + 1.128076553e+00f;
;     const f32x2 hv = v * 0.5f;
;     return hv * (x * p) + hv;
; }
;     __device__ __forceinline__ void operator()(const f32x4 (&acc)[2][2][4][2], const Unit& u, int wr, int wc, int fr, int fq) const {
;     ...
;             for (int m = 0; m < 4; ++m) { bf16_t* rowp = O + (size_t)(row0 + ai * HALF + m * 16) * ldc + col0;
;                 const float rs = rsqrtf(rsv[ai][m] * (1.f / 1024.f) + 1e-6f);
; #pragma unroll
;                 for (int bj = 0; bj < 2; ++bj) if (bj == 0 || !u.q) { f32x4 v0 = acc[ai][bj][m][0] * rs, v1 = acc[ai][bj][m][1] * rs;
;                     if (act) { f32x2 a = gelu_pk((f32x2){v0[0], v0[1]}), b = gelu_pk((f32x2){v0[2], v0[3]}), c = gelu_pk((f32x2){v1[0], v1[1]}), d = gelu_pk((f32x2){v1[2], v1[3]});
;                         v0 = (f32x4){a.x, a.y, b.x, b.y}; v1 = (f32x4){c.x, c.y, d.x, d.y}; }
;                     u32x4 w; w.x = cvt_pk_bf16(v0[0], v0[1]); w.y = cvt_pk_bf16(v0[2], v0[3]); w.z = cvt_pk_bf16(v1[0], v1[1]); w.w = cvt_pk_bf16(v1[2], v1[3]);
;                     *(u32x4*)(rowp + bj * HALF) = w; } }
.LBB0_107:
	v_readlane_b32 s2, v240, 12
	v_readlane_b32 s3, v240, 13
	v_mov_b32_e32 v97, v96
	v_cvt_pk_bf16_f32 v92, v92, v93
	v_cvt_pk_bf16_f32 v93, v94, v95
	v_cvt_pk_bf16_f32 v94, v98, v99
	v_cvt_pk_bf16_f32 v95, v90, v91
	s_nop 0
	v_mov_b64_e32 v[88:89], s[2:3]
	v_mad_i64_i32 v[88:89], s[2:3], v154, s91, v[88:89]
	v_mov_b32_e32 v90, v96
	v_mov_b32_e32 v91, v96
	v_lshl_add_u64 v[88:89], v[120:121], 1, v[88:89]
	v_pk_mul_f32 v[86:87], v[86:87], v[90:91]
	v_pk_mul_f32 v[84:85], v[84:85], v[96:97]
	v_pk_mul_f32 v[82:83], v[82:83], v[90:91]
	s_and_b64 vcc, exec, s[6:7]
	v_pk_mul_f32 v[80:81], v[80:81], v[96:97]
	global_store_dwordx4 v[88:89], v[92:95], off sc1
	s_cbranch_vccnz .LBB0_109
	v_pk_mul_f32 v[90:91], v[84:85], s[16:17] op_sel_hi:[1,0]
	v_mov_b64_e32 v[94:95], s[20:21]
	v_med3_f32 v90, v90, s90, v173
	v_med3_f32 v91, v91, s90, v173
	v_pk_mul_f32 v[92:93], v[90:91], v[90:91]
	v_pk_mul_f32 v[84:85], v[84:85], 0.5 op_sel_hi:[1,0]
	v_pk_fma_f32 v[96:97], v[92:93], s[18:19], v[94:95] op_sel_hi:[1,0,0] neg_lo:[1,0,0] neg_hi:[1,0,0]
	s_nop 0
	v_pk_fma_f32 v[96:97], v[92:93], v[96:97], s[28:29] op_sel_hi:[1,1,0]
	s_nop 0
	v_pk_fma_f32 v[96:97], v[92:93], v[96:97], s[30:31] op_sel_hi:[1,1,0]
	s_nop 0
	v_pk_fma_f32 v[96:97], v[92:93], v[96:97], s[34:35] op_sel_hi:[1,1,0]
	s_nop 0
	v_pk_fma_f32 v[96:97], v[92:93], v[96:97], s[36:37] op_sel_hi:[1,1,0]
	s_nop 0
	v_pk_fma_f32 v[96:97], v[92:93], v[96:97], s[38:39] op_sel_hi:[1,1,0]
	s_nop 0
	v_pk_fma_f32 v[92:93], v[92:93], v[96:97], s[40:41] op_sel_hi:[1,1,0]
	s_nop 0
	v_pk_mul_f32 v[90:91], v[90:91], v[92:93]
	s_nop 0
	v_pk_fma_f32 v[84:85], v[84:85], v[90:91], v[84:85]
	v_pk_mul_f32 v[90:91], v[86:87], s[16:17] op_sel_hi:[1,0]
	v_pk_mul_f32 v[86:87], v[86:87], 0.5 op_sel_hi:[1,0]
	v_med3_f32 v90, v90, s90, v173
	v_med3_f32 v91, v91, s90, v173
	v_pk_mul_f32 v[92:93], v[90:91], v[90:91]
	s_nop 0
	v_pk_fma_f32 v[96:97], v[92:93], s[18:19], v[94:95] op_sel_hi:[1,0,0] neg_lo:[1,0,0] neg_hi:[1,0,0]
	s_nop 0
	v_pk_fma_f32 v[96:97], v[92:93], v[96:97], s[28:29] op_sel_hi:[1,1,0]
	s_nop 0
	v_pk_fma_f32 v[96:97], v[92:93], v[96:97], s[30:31] op_sel_hi:[1,1,0]
	s_nop 0
	v_pk_fma_f32 v[96:97], v[92:93], v[96:97], s[34:35] op_sel_hi:[1,1,0]
	s_nop 0
	v_pk_fma_f32 v[96:97], v[92:93], v[96:97], s[36:37] op_sel_hi:[1,1,0]
	s_nop 0
	v_pk_fma_f32 v[96:97], v[92:93], v[96:97], s[38:39] op_sel_hi:[1,1,0]
	s_nop 0
	v_pk_fma_f32 v[92:93], v[92:93], v[96:97], s[40:41] op_sel_hi:[1,1,0]
	s_nop 0
	v_pk_mul_f32 v[90:91], v[90:91], v[92:93]
	s_nop 0
	v_pk_fma_f32 v[86:87], v[86:87], v[90:91], v[86:87]
	v_pk_mul_f32 v[90:91], v[80:81], s[16:17] op_sel_hi:[1,0]
	v_pk_mul_f32 v[80:81], v[80:81], 0.5 op_sel_hi:[1,0]
	v_med3_f32 v90, v90, s90, v173
	v_med3_f32 v91, v91, s90, v173
	v_pk_mul_f32 v[92:93], v[90:91], v[90:91]
	s_nop 0
	v_pk_fma_f32 v[96:97], v[92:93], s[18:19], v[94:95] op_sel_hi:[1,0,0] neg_lo:[1,0,0] neg_hi:[1,0,0]
	s_nop 0
	v_pk_fma_f32 v[96:97], v[92:93], v[96:97], s[28:29] op_sel_hi:[1,1,0]
	s_nop 0
	v_pk_fma_f32 v[96:97], v[92:93], v[96:97], s[30:31] op_sel_hi:[1,1,0]
	s_nop 0
	v_pk_fma_f32 v[96:97], v[92:93], v[96:97], s[34:35] op_sel_hi:[1,1,0]
	s_nop 0
	v_pk_fma_f32 v[96:97], v[92:93], v[96:97], s[36:37] op_sel_hi:[1,1,0]
	s_nop 0
	v_pk_fma_f32 v[96:97], v[92:93], v[96:97], s[38:39] op_sel_hi:[1,1,0]
	s_nop 0
	v_pk_fma_f32 v[92:93], v[92:93], v[96:97], s[40:41] op_sel_hi:[1,1,0]
	s_nop 0
	v_pk_mul_f32 v[90:91], v[90:91], v[92:93]
	s_nop 0
	v_pk_fma_f32 v[80:81], v[80:81], v[90:91], v[80:81]
	v_pk_mul_f32 v[90:91], v[82:83], s[16:17] op_sel_hi:[1,0]
	v_pk_mul_f32 v[82:83], v[82:83], 0.5 op_sel_hi:[1,0]
	v_med3_f32 v90, v90, s90, v173
	v_med3_f32 v91, v91, s90, v173
	v_pk_mul_f32 v[92:93], v[90:91], v[90:91]
	s_nop 0
	v_pk_fma_f32 v[94:95], v[92:93], s[18:19], v[94:95] op_sel_hi:[1,0,0] neg_lo:[1,0,0] neg_hi:[1,0,0]
	s_nop 0
	v_pk_fma_f32 v[94:95], v[92:93], v[94:95], s[28:29] op_sel_hi:[1,1,0]
	s_nop 0
	v_pk_fma_f32 v[94:95], v[92:93], v[94:95], s[30:31] op_sel_hi:[1,1,0]
	s_nop 0
	v_pk_fma_f32 v[94:95], v[92:93], v[94:95], s[34:35] op_sel_hi:[1,1,0]
	s_nop 0
	v_pk_fma_f32 v[94:95], v[92:93], v[94:95], s[36:37] op_sel_hi:[1,1,0]
	s_nop 0
	v_pk_fma_f32 v[94:95], v[92:93], v[94:95], s[38:39] op_sel_hi:[1,1,0]
	s_nop 0
	v_pk_fma_f32 v[92:93], v[92:93], v[94:95], s[40:41] op_sel_hi:[1,1,0]
	s_nop 0
	v_pk_mul_f32 v[90:91], v[90:91], v[92:93]
	s_nop 0
	v_pk_fma_f32 v[82:83], v[82:83], v[90:91], v[82:83]
; __device__ __forceinline__ unsigned cvt_pk_bf16(float lo, float hi) { unsigned r; asm volatile("v_cvt_pk_bf16_f32 %0, %1, %2" : "=v"(r) : "v"(lo), "v"(hi)); return r; }
; __device__ __forceinline__ f32x2 gelu_pk(f32x2 v) {
;     f32x2 x = v * 0.70710678118f;
;     x.x = __builtin_amdgcn_fmed3f(x.x, -2.9f, 2.9f); x.y = __builtin_amdgcn_fmed3f(x.y, -2.9f, 2.9f);
;     const f32x2 t = x * x;
;     f32x2 p = t * (-4.953124630e-07f) + 1.987094038e-05f;
;     p = p * t + (-3.472001117e-04f); p = p * t + 3.517547622e-03f; p = p * t + (-2.333305031e-02f); p = p * t + 1.087993085e-01f; p = p * t + (-3.740358949e-01f); p = p * t + 1.128076553e+00f;
;     const f32x2 hv = v * 0.5f;
;     return hv * (x * p) + hv;
; }
;     __device__ __forceinline__ void operator()(const f32x4 (&acc)[2][2][4][2], const Unit& u, int wr, int wc, int fr, int fq) const {
;     ...
;             for (int m = 0; m < 4; ++m) { bf16_t* rowp = O + (size_t)(row0 + ai * HALF + m * 16) * ldc + col0;
;                 const float rs = rsqrtf(rsv[ai][m] * (1.f / 1024.f) + 1e-6f);
; #pragma unroll
;                 for (int bj = 0; bj < 2; ++bj) if (bj == 0 || !u.q) { f32x4 v0 = acc[ai][bj][m][0] * rs, v1 = acc[ai][bj][m][1] * rs;
;                     if (act) { f32x2 a = gelu_pk((f32x2){v0[0], v0[1]}), b = gelu_pk((f32x2){v0[2], v0[3]}), c = gelu_pk((f32x2){v1[0], v1[1]}), d = gelu_pk((f32x2){v1[2], v1[3]});
;                         v0 = (f32x4){a.x, a.y, b.x, b.y}; v1 = (f32x4){c.x, c.y, d.x, d.y}; }
;                     u32x4 w; w.x = cvt_pk_bf16(v0[0], v0[1]); w.y = cvt_pk_bf16(v0[2], v0[3]); w.z = cvt_pk_bf16(v1[0], v1[1]); w.w = cvt_pk_bf16(v1[2], v1[3]);
;                     *(u32x4*)(rowp + bj * HALF) = w; } }
.LBB0_109:
	v_cvt_pk_bf16_f32 v84, v84, v85
	v_cvt_pk_bf16_f32 v85, v86, v87
	v_fmamk_f32 v86, v153, 0x3a800000, v172
	v_mul_f32_e32 v87, 0x4b800000, v86
	v_cmp_gt_f32_e32 vcc, s87, v86
	s_nop 1
	v_cndmask_b32_e32 v86, v86, v87, vcc
	v_rsq_f32_e32 v90, v86
	v_cvt_pk_bf16_f32 v86, v80, v81
	v_cvt_pk_bf16_f32 v87, v82, v83
	global_store_dwordx4 v[88:89], v[84:87], off offset:256 sc1
	v_mul_f32_e32 v80, 0x45800000, v90
	v_cndmask_b32_e32 v80, v90, v80, vcc
	v_pk_mul_f32 v[78:79], v[78:79], v[80:81] op_sel_hi:[1,0]
	v_pk_mul_f32 v[76:77], v[76:77], v[80:81] op_sel_hi:[1,0]
	v_pk_mul_f32 v[74:75], v[74:75], v[80:81] op_sel_hi:[1,0]
	s_and_b64 vcc, exec, s[6:7]
	v_pk_mul_f32 v[82:83], v[72:73], v[80:81] op_sel_hi:[1,0]
	s_cbranch_vccnz .LBB0_111
	v_pk_mul_f32 v[72:73], v[76:77], s[16:17] op_sel_hi:[1,0]
	v_mov_b64_e32 v[86:87], s[20:21]
	v_med3_f32 v72, v72, s90, v173
	v_med3_f32 v73, v73, s90, v173
	v_pk_mul_f32 v[84:85], v[72:73], v[72:73]
	v_pk_mul_f32 v[76:77], v[76:77], 0.5 op_sel_hi:[1,0]
	v_pk_fma_f32 v[88:89], v[84:85], s[18:19], v[86:87] op_sel_hi:[1,0,0] neg_lo:[1,0,0] neg_hi:[1,0,0]
	s_nop 0
	v_pk_fma_f32 v[88:89], v[84:85], v[88:89], s[28:29] op_sel_hi:[1,1,0]
	s_nop 0
	v_pk_fma_f32 v[88:89], v[84:85], v[88:89], s[30:31] op_sel_hi:[1,1,0]
	s_nop 0
	v_pk_fma_f32 v[88:89], v[84:85], v[88:89], s[34:35] op_sel_hi:[1,1,0]
	s_nop 0
	v_pk_fma_f32 v[88:89], v[84:85], v[88:89], s[36:37] op_sel_hi:[1,1,0]
	s_nop 0
	v_pk_fma_f32 v[88:89], v[84:85], v[88:89], s[38:39] op_sel_hi:[1,1,0]
	s_nop 0
	v_pk_fma_f32 v[84:85], v[84:85], v[88:89], s[40:41] op_sel_hi:[1,1,0]
	s_nop 0
	v_pk_mul_f32 v[72:73], v[72:73], v[84:85]
	s_nop 0
	v_pk_fma_f32 v[76:77], v[76:77], v[72:73], v[76:77]
	v_pk_mul_f32 v[72:73], v[78:79], s[16:17] op_sel_hi:[1,0]
	v_pk_mul_f32 v[78:79], v[78:79], 0.5 op_sel_hi:[1,0]
	v_med3_f32 v72, v72, s90, v173
	v_med3_f32 v73, v73, s90, v173
	v_pk_mul_f32 v[84:85], v[72:73], v[72:73]
	s_nop 0
	v_pk_fma_f32 v[88:89], v[84:85], s[18:19], v[86:87] op_sel_hi:[1,0,0] neg_lo:[1,0,0] neg_hi:[1,0,0]
	s_nop 0
	v_pk_fma_f32 v[88:89], v[84:85], v[88:89], s[28:29] op_sel_hi:[1,1,0]
	s_nop 0
	v_pk_fma_f32 v[88:89], v[84:85], v[88:89], s[30:31] op_sel_hi:[1,1,0]
	s_nop 0
	v_pk_fma_f32 v[88:89], v[84:85], v[88:89], s[34:35] op_sel_hi:[1,1,0]
	s_nop 0
	v_pk_fma_f32 v[88:89], v[84:85], v[88:89], s[36:37] op_sel_hi:[1,1,0]
	s_nop 0
	v_pk_fma_f32 v[88:89], v[84:85], v[88:89], s[38:39] op_sel_hi:[1,1,0]
	s_nop 0
	v_pk_fma_f32 v[84:85], v[84:85], v[88:89], s[40:41] op_sel_hi:[1,1,0]
	s_nop 0
	v_pk_mul_f32 v[72:73], v[72:73], v[84:85]
	s_nop 0
	v_pk_fma_f32 v[78:79], v[78:79], v[72:73], v[78:79]
	v_pk_mul_f32 v[72:73], v[82:83], s[16:17] op_sel_hi:[1,0]
	v_pk_mul_f32 v[82:83], v[82:83], 0.5 op_sel_hi:[1,0]
	v_med3_f32 v72, v72, s90, v173
	v_med3_f32 v73, v73, s90, v173
	v_pk_mul_f32 v[84:85], v[72:73], v[72:73]
	s_nop 0
	v_pk_fma_f32 v[88:89], v[84:85], s[18:19], v[86:87] op_sel_hi:[1,0,0] neg_lo:[1,0,0] neg_hi:[1,0,0]
	s_nop 0
	v_pk_fma_f32 v[88:89], v[84:85], v[88:89], s[28:29] op_sel_hi:[1,1,0]
	s_nop 0
	v_pk_fma_f32 v[88:89], v[84:85], v[88:89], s[30:31] op_sel_hi:[1,1,0]
	s_nop 0
	v_pk_fma_f32 v[88:89], v[84:85], v[88:89], s[34:35] op_sel_hi:[1,1,0]
	s_nop 0
	v_pk_fma_f32 v[88:89], v[84:85], v[88:89], s[36:37] op_sel_hi:[1,1,0]
	s_nop 0
	v_pk_fma_f32 v[88:89], v[84:85], v[88:89], s[38:39] op_sel_hi:[1,1,0]
	s_nop 0
	v_pk_fma_f32 v[84:85], v[84:85], v[88:89], s[40:41] op_sel_hi:[1,1,0]
	s_nop 0
	v_pk_mul_f32 v[72:73], v[72:73], v[84:85]
	s_nop 0
	v_pk_fma_f32 v[82:83], v[82:83], v[72:73], v[82:83]
	v_pk_mul_f32 v[72:73], v[74:75], s[16:17] op_sel_hi:[1,0]
	v_pk_mul_f32 v[74:75], v[74:75], 0.5 op_sel_hi:[1,0]
	v_med3_f32 v72, v72, s90, v173
	v_med3_f32 v73, v73, s90, v173
	v_pk_mul_f32 v[84:85], v[72:73], v[72:73]
	s_nop 0
	v_pk_fma_f32 v[86:87], v[84:85], s[18:19], v[86:87] op_sel_hi:[1,0,0] neg_lo:[1,0,0] neg_hi:[1,0,0]
	s_nop 0
	v_pk_fma_f32 v[86:87], v[84:85], v[86:87], s[28:29] op_sel_hi:[1,1,0]
	s_nop 0
	v_pk_fma_f32 v[86:87], v[84:85], v[86:87], s[30:31] op_sel_hi:[1,1,0]
	s_nop 0
	v_pk_fma_f32 v[86:87], v[84:85], v[86:87], s[34:35] op_sel_hi:[1,1,0]
	s_nop 0
	v_pk_fma_f32 v[86:87], v[84:85], v[86:87], s[36:37] op_sel_hi:[1,1,0]
	s_nop 0
	v_pk_fma_f32 v[86:87], v[84:85], v[86:87], s[38:39] op_sel_hi:[1,1,0]
	s_nop 0
	v_pk_fma_f32 v[84:85], v[84:85], v[86:87], s[40:41] op_sel_hi:[1,1,0]
	s_nop 0
	v_pk_mul_f32 v[72:73], v[72:73], v[84:85]
	s_nop 0
	v_pk_fma_f32 v[74:75], v[74:75], v[72:73], v[74:75]
; __device__ __forceinline__ unsigned cvt_pk_bf16(float lo, float hi) { unsigned r; asm volatile("v_cvt_pk_bf16_f32 %0, %1, %2" : "=v"(r) : "v"(lo), "v"(hi)); return r; }
; __device__ __forceinline__ f32x2 gelu_pk(f32x2 v) {
;     f32x2 x = v * 0.70710678118f;
;     x.x = __builtin_amdgcn_fmed3f(x.x, -2.9f, 2.9f); x.y = __builtin_amdgcn_fmed3f(x.y, -2.9f, 2.9f);
;     const f32x2 t = x * x;
;     f32x2 p = t * (-4.953124630e-07f) + 1.987094038e-05f;
;     p = p * t + (-3.472001117e-04f); p = p * t + 3.517547622e-03f; p = p * t + (-2.333305031e-02f); p = p * t + 1.087993085e-01f; p = p * t + (-3.740358949e-01f); p = p * t + 1.128076553e+00f;
;     const f32x2 hv = v * 0.5f;
;     return hv * (x * p) + hv;
; }
;     __device__ __forceinline__ void operator()(const f32x4 (&acc)[2][2][4][2], const Unit& u, int wr, int wc, int fr, int fq) const {
;     ...
;             for (int m = 0; m < 4; ++m) { bf16_t* rowp = O + (size_t)(row0 + ai * HALF + m * 16) * ldc + col0;
;                 const float rs = rsqrtf(rsv[ai][m] * (1.f / 1024.f) + 1e-6f);
; #pragma unroll
;                 for (int bj = 0; bj < 2; ++bj) if (bj == 0 || !u.q) { f32x4 v0 = acc[ai][bj][m][0] * rs, v1 = acc[ai][bj][m][1] * rs;
;                     if (act) { f32x2 a = gelu_pk((f32x2){v0[0], v0[1]}), b = gelu_pk((f32x2){v0[2], v0[3]}), c = gelu_pk((f32x2){v1[0], v1[1]}), d = gelu_pk((f32x2){v1[2], v1[3]});
;                         v0 = (f32x4){a.x, a.y, b.x, b.y}; v1 = (f32x4){c.x, c.y, d.x, d.y}; }
;                     u32x4 w; w.x = cvt_pk_bf16(v0[0], v0[1]); w.y = cvt_pk_bf16(v0[2], v0[3]); w.z = cvt_pk_bf16(v1[0], v1[1]); w.w = cvt_pk_bf16(v1[2], v1[3]);
;                     *(u32x4*)(rowp + bj * HALF) = w; } }
.LBB0_111:
	v_readlane_b32 s2, v240, 12
	v_readlane_b32 s3, v240, 13
	v_mov_b32_e32 v81, v80
	v_cvt_pk_bf16_f32 v76, v76, v77
	v_cvt_pk_bf16_f32 v77, v78, v79
	v_cvt_pk_bf16_f32 v78, v82, v83
	v_cvt_pk_bf16_f32 v79, v74, v75
	s_nop 0
	v_mov_b64_e32 v[72:73], s[2:3]
	v_mad_i64_i32 v[72:73], s[2:3], v152, s91, v[72:73]
	v_mov_b32_e32 v74, v80
	v_mov_b32_e32 v75, v80
	v_lshl_add_u64 v[72:73], v[120:121], 1, v[72:73]
	v_pk_mul_f32 v[70:71], v[70:71], v[74:75]
	v_pk_mul_f32 v[68:69], v[68:69], v[80:81]
	v_pk_mul_f32 v[66:67], v[66:67], v[74:75]
	s_and_b64 vcc, exec, s[6:7]
	v_pk_mul_f32 v[64:65], v[64:65], v[80:81]
	global_store_dwordx4 v[72:73], v[76:79], off sc1
	s_cbranch_vccnz .LBB0_113
	v_pk_mul_f32 v[74:75], v[68:69], s[16:17] op_sel_hi:[1,0]
	v_mov_b64_e32 v[78:79], s[20:21]
	v_med3_f32 v74, v74, s90, v173
	v_med3_f32 v75, v75, s90, v173
	v_pk_mul_f32 v[76:77], v[74:75], v[74:75]
	v_pk_mul_f32 v[68:69], v[68:69], 0.5 op_sel_hi:[1,0]
	v_pk_fma_f32 v[80:81], v[76:77], s[18:19], v[78:79] op_sel_hi:[1,0,0] neg_lo:[1,0,0] neg_hi:[1,0,0]
	s_nop 0
	v_pk_fma_f32 v[80:81], v[76:77], v[80:81], s[28:29] op_sel_hi:[1,1,0]
	s_nop 0
	v_pk_fma_f32 v[80:81], v[76:77], v[80:81], s[30:31] op_sel_hi:[1,1,0]
	s_nop 0
	v_pk_fma_f32 v[80:81], v[76:77], v[80:81], s[34:35] op_sel_hi:[1,1,0]
	s_nop 0
	v_pk_fma_f32 v[80:81], v[76:77], v[80:81], s[36:37] op_sel_hi:[1,1,0]
	s_nop 0
	v_pk_fma_f32 v[80:81], v[76:77], v[80:81], s[38:39] op_sel_hi:[1,1,0]
	s_nop 0
	v_pk_fma_f32 v[76:77], v[76:77], v[80:81], s[40:41] op_sel_hi:[1,1,0]
	s_nop 0
	v_pk_mul_f32 v[74:75], v[74:75], v[76:77]
	s_nop 0
	v_pk_fma_f32 v[68:69], v[68:69], v[74:75], v[68:69]
	v_pk_mul_f32 v[74:75], v[70:71], s[16:17] op_sel_hi:[1,0]
	v_pk_mul_f32 v[70:71], v[70:71], 0.5 op_sel_hi:[1,0]
	v_med3_f32 v74, v74, s90, v173
	v_med3_f32 v75, v75, s90, v173
	v_pk_mul_f32 v[76:77], v[74:75], v[74:75]
	s_nop 0
	v_pk_fma_f32 v[80:81], v[76:77], s[18:19], v[78:79] op_sel_hi:[1,0,0] neg_lo:[1,0,0] neg_hi:[1,0,0]
	s_nop 0
	v_pk_fma_f32 v[80:81], v[76:77], v[80:81], s[28:29] op_sel_hi:[1,1,0]
	s_nop 0
	v_pk_fma_f32 v[80:81], v[76:77], v[80:81], s[30:31] op_sel_hi:[1,1,0]
	s_nop 0
	v_pk_fma_f32 v[80:81], v[76:77], v[80:81], s[34:35] op_sel_hi:[1,1,0]
	s_nop 0
	v_pk_fma_f32 v[80:81], v[76:77], v[80:81], s[36:37] op_sel_hi:[1,1,0]
	s_nop 0
	v_pk_fma_f32 v[80:81], v[76:77], v[80:81], s[38:39] op_sel_hi:[1,1,0]
	s_nop 0
	v_pk_fma_f32 v[76:77], v[76:77], v[80:81], s[40:41] op_sel_hi:[1,1,0]
	s_nop 0
	v_pk_mul_f32 v[74:75], v[74:75], v[76:77]
	s_nop 0
	v_pk_fma_f32 v[70:71], v[70:71], v[74:75], v[70:71]
	v_pk_mul_f32 v[74:75], v[64:65], s[16:17] op_sel_hi:[1,0]
	v_pk_mul_f32 v[64:65], v[64:65], 0.5 op_sel_hi:[1,0]
	v_med3_f32 v74, v74, s90, v173
	v_med3_f32 v75, v75, s90, v173
	v_pk_mul_f32 v[76:77], v[74:75], v[74:75]
	s_nop 0
	v_pk_fma_f32 v[80:81], v[76:77], s[18:19], v[78:79] op_sel_hi:[1,0,0] neg_lo:[1,0,0] neg_hi:[1,0,0]
	s_nop 0
	v_pk_fma_f32 v[80:81], v[76:77], v[80:81], s[28:29] op_sel_hi:[1,1,0]
	s_nop 0
	v_pk_fma_f32 v[80:81], v[76:77], v[80:81], s[30:31] op_sel_hi:[1,1,0]
	s_nop 0
	v_pk_fma_f32 v[80:81], v[76:77], v[80:81], s[34:35] op_sel_hi:[1,1,0]
	s_nop 0
	v_pk_fma_f32 v[80:81], v[76:77], v[80:81], s[36:37] op_sel_hi:[1,1,0]
	s_nop 0
	v_pk_fma_f32 v[80:81], v[76:77], v[80:81], s[38:39] op_sel_hi:[1,1,0]
	s_nop 0
	v_pk_fma_f32 v[76:77], v[76:77], v[80:81], s[40:41] op_sel_hi:[1,1,0]
	s_nop 0
	v_pk_mul_f32 v[74:75], v[74:75], v[76:77]
	s_nop 0
	v_pk_fma_f32 v[64:65], v[64:65], v[74:75], v[64:65]
	v_pk_mul_f32 v[74:75], v[66:67], s[16:17] op_sel_hi:[1,0]
	v_pk_mul_f32 v[66:67], v[66:67], 0.5 op_sel_hi:[1,0]
	v_med3_f32 v74, v74, s90, v173
	v_med3_f32 v75, v75, s90, v173
	v_pk_mul_f32 v[76:77], v[74:75], v[74:75]
	s_nop 0
	v_pk_fma_f32 v[78:79], v[76:77], s[18:19], v[78:79] op_sel_hi:[1,0,0] neg_lo:[1,0,0] neg_hi:[1,0,0]
	s_nop 0
	v_pk_fma_f32 v[78:79], v[76:77], v[78:79], s[28:29] op_sel_hi:[1,1,0]
	s_nop 0
	v_pk_fma_f32 v[78:79], v[76:77], v[78:79], s[30:31] op_sel_hi:[1,1,0]
	s_nop 0
	v_pk_fma_f32 v[78:79], v[76:77], v[78:79], s[34:35] op_sel_hi:[1,1,0]
	s_nop 0
	v_pk_fma_f32 v[78:79], v[76:77], v[78:79], s[36:37] op_sel_hi:[1,1,0]
	s_nop 0
	v_pk_fma_f32 v[78:79], v[76:77], v[78:79], s[38:39] op_sel_hi:[1,1,0]
	s_nop 0
	v_pk_fma_f32 v[76:77], v[76:77], v[78:79], s[40:41] op_sel_hi:[1,1,0]
	s_nop 0
	v_pk_mul_f32 v[74:75], v[74:75], v[76:77]
	s_nop 0
	v_pk_fma_f32 v[66:67], v[66:67], v[74:75], v[66:67]
; __device__ __forceinline__ unsigned cvt_pk_bf16(float lo, float hi) { unsigned r; asm volatile("v_cvt_pk_bf16_f32 %0, %1, %2" : "=v"(r) : "v"(lo), "v"(hi)); return r; }
; __device__ __forceinline__ f32x2 gelu_pk(f32x2 v) {
;     f32x2 x = v * 0.70710678118f;
;     x.x = __builtin_amdgcn_fmed3f(x.x, -2.9f, 2.9f); x.y = __builtin_amdgcn_fmed3f(x.y, -2.9f, 2.9f);
;     const f32x2 t = x * x;
;     f32x2 p = t * (-4.953124630e-07f) + 1.987094038e-05f;
;     p = p * t + (-3.472001117e-04f); p = p * t + 3.517547622e-03f; p = p * t + (-2.333305031e-02f); p = p * t + 1.087993085e-01f; p = p * t + (-3.740358949e-01f); p = p * t + 1.128076553e+00f;
;     const f32x2 hv = v * 0.5f;
;     return hv * (x * p) + hv;
; }
;     __device__ __forceinline__ void operator()(const f32x4 (&acc)[2][2][4][2], const Unit& u, int wr, int wc, int fr, int fq) const {
;     ...
;             for (int m = 0; m < 4; ++m) { bf16_t* rowp = O + (size_t)(row0 + ai * HALF + m * 16) * ldc + col0;
;                 const float rs = rsqrtf(rsv[ai][m] * (1.f / 1024.f) + 1e-6f);
; #pragma unroll
;                 for (int bj = 0; bj < 2; ++bj) if (bj == 0 || !u.q) { f32x4 v0 = acc[ai][bj][m][0] * rs, v1 = acc[ai][bj][m][1] * rs;
;                     if (act) { f32x2 a = gelu_pk((f32x2){v0[0], v0[1]}), b = gelu_pk((f32x2){v0[2], v0[3]}), c = gelu_pk((f32x2){v1[0], v1[1]}), d = gelu_pk((f32x2){v1[2], v1[3]});
;                         v0 = (f32x4){a.x, a.y, b.x, b.y}; v1 = (f32x4){c.x, c.y, d.x, d.y}; }
;                     u32x4 w; w.x = cvt_pk_bf16(v0[0], v0[1]); w.y = cvt_pk_bf16(v0[2], v0[3]); w.z = cvt_pk_bf16(v1[0], v1[1]); w.w = cvt_pk_bf16(v1[2], v1[3]);
;                     *(u32x4*)(rowp + bj * HALF) = w; } }
.LBB0_113:
	v_cvt_pk_bf16_f32 v68, v68, v69
	v_cvt_pk_bf16_f32 v69, v70, v71
	v_fmamk_f32 v70, v151, 0x3a800000, v172
	v_mul_f32_e32 v71, 0x4b800000, v70
	v_cmp_gt_f32_e32 vcc, s87, v70
	s_nop 1
	v_cndmask_b32_e32 v70, v70, v71, vcc
	v_rsq_f32_e32 v74, v70
	v_cvt_pk_bf16_f32 v70, v64, v65
	v_cvt_pk_bf16_f32 v71, v66, v67
	global_store_dwordx4 v[72:73], v[68:71], off offset:256 sc1
	v_mul_f32_e32 v64, 0x45800000, v74
	v_cndmask_b32_e32 v64, v74, v64, vcc
	v_pk_mul_f32 v[62:63], v[62:63], v[64:65] op_sel_hi:[1,0]
	v_pk_mul_f32 v[60:61], v[60:61], v[64:65] op_sel_hi:[1,0]
	v_pk_mul_f32 v[58:59], v[58:59], v[64:65] op_sel_hi:[1,0]
	s_and_b64 vcc, exec, s[6:7]
	v_pk_mul_f32 v[66:67], v[56:57], v[64:65] op_sel_hi:[1,0]
	s_cbranch_vccnz .LBB0_115
	v_pk_mul_f32 v[56:57], v[60:61], s[16:17] op_sel_hi:[1,0]
	v_mov_b64_e32 v[70:71], s[20:21]
	v_med3_f32 v56, v56, s90, v173
	v_med3_f32 v57, v57, s90, v173
	v_pk_mul_f32 v[68:69], v[56:57], v[56:57]
	v_pk_mul_f32 v[60:61], v[60:61], 0.5 op_sel_hi:[1,0]
	v_pk_fma_f32 v[72:73], v[68:69], s[18:19], v[70:71] op_sel_hi:[1,0,0] neg_lo:[1,0,0] neg_hi:[1,0,0]
	s_nop 0
	v_pk_fma_f32 v[72:73], v[68:69], v[72:73], s[28:29] op_sel_hi:[1,1,0]
	s_nop 0
	v_pk_fma_f32 v[72:73], v[68:69], v[72:73], s[30:31] op_sel_hi:[1,1,0]
	s_nop 0
	v_pk_fma_f32 v[72:73], v[68:69], v[72:73], s[34:35] op_sel_hi:[1,1,0]
	s_nop 0
	v_pk_fma_f32 v[72:73], v[68:69], v[72:73], s[36:37] op_sel_hi:[1,1,0]
	s_nop 0
	v_pk_fma_f32 v[72:73], v[68:69], v[72:73], s[38:39] op_sel_hi:[1,1,0]
	s_nop 0
	v_pk_fma_f32 v[68:69], v[68:69], v[72:73], s[40:41] op_sel_hi:[1,1,0]
	s_nop 0
	v_pk_mul_f32 v[56:57], v[56:57], v[68:69]
	s_nop 0
	v_pk_fma_f32 v[60:61], v[60:61], v[56:57], v[60:61]
	v_pk_mul_f32 v[56:57], v[62:63], s[16:17] op_sel_hi:[1,0]
	v_pk_mul_f32 v[62:63], v[62:63], 0.5 op_sel_hi:[1,0]
	v_med3_f32 v56, v56, s90, v173
	v_med3_f32 v57, v57, s90, v173
	v_pk_mul_f32 v[68:69], v[56:57], v[56:57]
	s_nop 0
	v_pk_fma_f32 v[72:73], v[68:69], s[18:19], v[70:71] op_sel_hi:[1,0,0] neg_lo:[1,0,0] neg_hi:[1,0,0]
	s_nop 0
	v_pk_fma_f32 v[72:73], v[68:69], v[72:73], s[28:29] op_sel_hi:[1,1,0]
	s_nop 0
	v_pk_fma_f32 v[72:73], v[68:69], v[72:73], s[30:31] op_sel_hi:[1,1,0]
	s_nop 0
	v_pk_fma_f32 v[72:73], v[68:69], v[72:73], s[34:35] op_sel_hi:[1,1,0]
	s_nop 0
	v_pk_fma_f32 v[72:73], v[68:69], v[72:73], s[36:37] op_sel_hi:[1,1,0]
	s_nop 0
	v_pk_fma_f32 v[72:73], v[68:69], v[72:73], s[38:39] op_sel_hi:[1,1,0]
	s_nop 0
	v_pk_fma_f32 v[68:69], v[68:69], v[72:73], s[40:41] op_sel_hi:[1,1,0]
	s_nop 0
	v_pk_mul_f32 v[56:57], v[56:57], v[68:69]
	s_nop 0
	v_pk_fma_f32 v[62:63], v[62:63], v[56:57], v[62:63]
	v_pk_mul_f32 v[56:57], v[66:67], s[16:17] op_sel_hi:[1,0]
	v_pk_mul_f32 v[66:67], v[66:67], 0.5 op_sel_hi:[1,0]
	v_med3_f32 v56, v56, s90, v173
	v_med3_f32 v57, v57, s90, v173
	v_pk_mul_f32 v[68:69], v[56:57], v[56:57]
	s_nop 0
	v_pk_fma_f32 v[72:73], v[68:69], s[18:19], v[70:71] op_sel_hi:[1,0,0] neg_lo:[1,0,0] neg_hi:[1,0,0]
	s_nop 0
	v_pk_fma_f32 v[72:73], v[68:69], v[72:73], s[28:29] op_sel_hi:[1,1,0]
	s_nop 0
	v_pk_fma_f32 v[72:73], v[68:69], v[72:73], s[30:31] op_sel_hi:[1,1,0]
	s_nop 0
	v_pk_fma_f32 v[72:73], v[68:69], v[72:73], s[34:35] op_sel_hi:[1,1,0]
	s_nop 0
	v_pk_fma_f32 v[72:73], v[68:69], v[72:73], s[36:37] op_sel_hi:[1,1,0]
	s_nop 0
	v_pk_fma_f32 v[72:73], v[68:69], v[72:73], s[38:39] op_sel_hi:[1,1,0]
	s_nop 0
	v_pk_fma_f32 v[68:69], v[68:69], v[72:73], s[40:41] op_sel_hi:[1,1,0]
	s_nop 0
	v_pk_mul_f32 v[56:57], v[56:57], v[68:69]
	s_nop 0
	v_pk_fma_f32 v[66:67], v[66:67], v[56:57], v[66:67]
	v_pk_mul_f32 v[56:57], v[58:59], s[16:17] op_sel_hi:[1,0]
	v_pk_mul_f32 v[58:59], v[58:59], 0.5 op_sel_hi:[1,0]
	v_med3_f32 v56, v56, s90, v173
	v_med3_f32 v57, v57, s90, v173
	v_pk_mul_f32 v[68:69], v[56:57], v[56:57]
	s_nop 0
	v_pk_fma_f32 v[70:71], v[68:69], s[18:19], v[70:71] op_sel_hi:[1,0,0] neg_lo:[1,0,0] neg_hi:[1,0,0]
	s_nop 0
	v_pk_fma_f32 v[70:71], v[68:69], v[70:71], s[28:29] op_sel_hi:[1,1,0]
	s_nop 0
	v_pk_fma_f32 v[70:71], v[68:69], v[70:71], s[30:31] op_sel_hi:[1,1,0]
	s_nop 0
	v_pk_fma_f32 v[70:71], v[68:69], v[70:71], s[34:35] op_sel_hi:[1,1,0]
	s_nop 0
	v_pk_fma_f32 v[70:71], v[68:69], v[70:71], s[36:37] op_sel_hi:[1,1,0]
	s_nop 0
	v_pk_fma_f32 v[70:71], v[68:69], v[70:71], s[38:39] op_sel_hi:[1,1,0]
	s_nop 0
	v_pk_fma_f32 v[68:69], v[68:69], v[70:71], s[40:41] op_sel_hi:[1,1,0]
	s_nop 0
	v_pk_mul_f32 v[56:57], v[56:57], v[68:69]
	s_nop 0
	v_pk_fma_f32 v[58:59], v[58:59], v[56:57], v[58:59]
; __device__ __forceinline__ unsigned cvt_pk_bf16(float lo, float hi) { unsigned r; asm volatile("v_cvt_pk_bf16_f32 %0, %1, %2" : "=v"(r) : "v"(lo), "v"(hi)); return r; }
; __device__ __forceinline__ f32x2 gelu_pk(f32x2 v) {
;     f32x2 x = v * 0.70710678118f;
;     x.x = __builtin_amdgcn_fmed3f(x.x, -2.9f, 2.9f); x.y = __builtin_amdgcn_fmed3f(x.y, -2.9f, 2.9f);
;     const f32x2 t = x * x;
;     f32x2 p = t * (-4.953124630e-07f) + 1.987094038e-05f;
;     p = p * t + (-3.472001117e-04f); p = p * t + 3.517547622e-03f; p = p * t + (-2.333305031e-02f); p = p * t + 1.087993085e-01f; p = p * t + (-3.740358949e-01f); p = p * t + 1.128076553e+00f;
;     const f32x2 hv = v * 0.5f;
;     return hv * (x * p) + hv;
; }
;     __device__ __forceinline__ void operator()(const f32x4 (&acc)[2][2][4][2], const Unit& u, int wr, int wc, int fr, int fq) const {
;     ...
;             for (int m = 0; m < 4; ++m) { bf16_t* rowp = O + (size_t)(row0 + ai * HALF + m * 16) * ldc + col0;
;                 const float rs = rsqrtf(rsv[ai][m] * (1.f / 1024.f) + 1e-6f);
; #pragma unroll
;                 for (int bj = 0; bj < 2; ++bj) if (bj == 0 || !u.q) { f32x4 v0 = acc[ai][bj][m][0] * rs, v1 = acc[ai][bj][m][1] * rs;
;                     if (act) { f32x2 a = gelu_pk((f32x2){v0[0], v0[1]}), b = gelu_pk((f32x2){v0[2], v0[3]}), c = gelu_pk((f32x2){v1[0], v1[1]}), d = gelu_pk((f32x2){v1[2], v1[3]});
;                         v0 = (f32x4){a.x, a.y, b.x, b.y}; v1 = (f32x4){c.x, c.y, d.x, d.y}; }
;                     u32x4 w; w.x = cvt_pk_bf16(v0[0], v0[1]); w.y = cvt_pk_bf16(v0[2], v0[3]); w.z = cvt_pk_bf16(v1[0], v1[1]); w.w = cvt_pk_bf16(v1[2], v1[3]);
;                     *(u32x4*)(rowp + bj * HALF) = w; } }
.LBB0_115:
	v_readlane_b32 s2, v240, 12
	v_readlane_b32 s3, v240, 13
	v_mov_b32_e32 v65, v64
	v_cvt_pk_bf16_f32 v60, v60, v61
	v_cvt_pk_bf16_f32 v61, v62, v63
	v_cvt_pk_bf16_f32 v62, v66, v67
	v_cvt_pk_bf16_f32 v63, v58, v59
	s_nop 0
	v_mov_b64_e32 v[56:57], s[2:3]
	v_mad_i64_i32 v[56:57], s[2:3], v150, s91, v[56:57]
	v_mov_b32_e32 v58, v64
	v_mov_b32_e32 v59, v64
	v_lshl_add_u64 v[56:57], v[120:121], 1, v[56:57]
	v_pk_mul_f32 v[54:55], v[54:55], v[58:59]
	v_pk_mul_f32 v[52:53], v[52:53], v[64:65]
	v_pk_mul_f32 v[50:51], v[50:51], v[58:59]
	s_and_b64 vcc, exec, s[6:7]
	v_pk_mul_f32 v[48:49], v[48:49], v[64:65]
	global_store_dwordx4 v[56:57], v[60:63], off sc1
	s_cbranch_vccnz .LBB0_117
	v_pk_mul_f32 v[58:59], v[52:53], s[16:17] op_sel_hi:[1,0]
	v_mov_b64_e32 v[62:63], s[20:21]
	v_med3_f32 v58, v58, s90, v173
	v_med3_f32 v59, v59, s90, v173
	v_pk_mul_f32 v[60:61], v[58:59], v[58:59]
	v_pk_mul_f32 v[52:53], v[52:53], 0.5 op_sel_hi:[1,0]
	v_pk_fma_f32 v[64:65], v[60:61], s[18:19], v[62:63] op_sel_hi:[1,0,0] neg_lo:[1,0,0] neg_hi:[1,0,0]
	s_nop 0
	v_pk_fma_f32 v[64:65], v[60:61], v[64:65], s[28:29] op_sel_hi:[1,1,0]
	s_nop 0
	v_pk_fma_f32 v[64:65], v[60:61], v[64:65], s[30:31] op_sel_hi:[1,1,0]
	s_nop 0
	v_pk_fma_f32 v[64:65], v[60:61], v[64:65], s[34:35] op_sel_hi:[1,1,0]
	s_nop 0
	v_pk_fma_f32 v[64:65], v[60:61], v[64:65], s[36:37] op_sel_hi:[1,1,0]
	s_nop 0
	v_pk_fma_f32 v[64:65], v[60:61], v[64:65], s[38:39] op_sel_hi:[1,1,0]
	s_nop 0
	v_pk_fma_f32 v[60:61], v[60:61], v[64:65], s[40:41] op_sel_hi:[1,1,0]
	s_nop 0
	v_pk_mul_f32 v[58:59], v[58:59], v[60:61]
	s_nop 0
	v_pk_fma_f32 v[52:53], v[52:53], v[58:59], v[52:53]
	v_pk_mul_f32 v[58:59], v[54:55], s[16:17] op_sel_hi:[1,0]
	v_pk_mul_f32 v[54:55], v[54:55], 0.5 op_sel_hi:[1,0]
	v_med3_f32 v58, v58, s90, v173
	v_med3_f32 v59, v59, s90, v173
	v_pk_mul_f32 v[60:61], v[58:59], v[58:59]
	s_nop 0
	v_pk_fma_f32 v[64:65], v[60:61], s[18:19], v[62:63] op_sel_hi:[1,0,0] neg_lo:[1,0,0] neg_hi:[1,0,0]
	s_nop 0
	v_pk_fma_f32 v[64:65], v[60:61], v[64:65], s[28:29] op_sel_hi:[1,1,0]
	s_nop 0
	v_pk_fma_f32 v[64:65], v[60:61], v[64:65], s[30:31] op_sel_hi:[1,1,0]
	s_nop 0
	v_pk_fma_f32 v[64:65], v[60:61], v[64:65], s[34:35] op_sel_hi:[1,1,0]
	s_nop 0
	v_pk_fma_f32 v[64:65], v[60:61], v[64:65], s[36:37] op_sel_hi:[1,1,0]
	s_nop 0
	v_pk_fma_f32 v[64:65], v[60:61], v[64:65], s[38:39] op_sel_hi:[1,1,0]
	s_nop 0
	v_pk_fma_f32 v[60:61], v[60:61], v[64:65], s[40:41] op_sel_hi:[1,1,0]
	s_nop 0
	v_pk_mul_f32 v[58:59], v[58:59], v[60:61]
	s_nop 0
	v_pk_fma_f32 v[54:55], v[54:55], v[58:59], v[54:55]
	v_pk_mul_f32 v[58:59], v[48:49], s[16:17] op_sel_hi:[1,0]
	v_pk_mul_f32 v[48:49], v[48:49], 0.5 op_sel_hi:[1,0]
	v_med3_f32 v58, v58, s90, v173
	v_med3_f32 v59, v59, s90, v173
	v_pk_mul_f32 v[60:61], v[58:59], v[58:59]
	s_nop 0
	v_pk_fma_f32 v[64:65], v[60:61], s[18:19], v[62:63] op_sel_hi:[1,0,0] neg_lo:[1,0,0] neg_hi:[1,0,0]
	s_nop 0
	v_pk_fma_f32 v[64:65], v[60:61], v[64:65], s[28:29] op_sel_hi:[1,1,0]
	s_nop 0
	v_pk_fma_f32 v[64:65], v[60:61], v[64:65], s[30:31] op_sel_hi:[1,1,0]
	s_nop 0
	v_pk_fma_f32 v[64:65], v[60:61], v[64:65], s[34:35] op_sel_hi:[1,1,0]
	s_nop 0
	v_pk_fma_f32 v[64:65], v[60:61], v[64:65], s[36:37] op_sel_hi:[1,1,0]
	s_nop 0
	v_pk_fma_f32 v[64:65], v[60:61], v[64:65], s[38:39] op_sel_hi:[1,1,0]
	s_nop 0
	v_pk_fma_f32 v[60:61], v[60:61], v[64:65], s[40:41] op_sel_hi:[1,1,0]
	s_nop 0
	v_pk_mul_f32 v[58:59], v[58:59], v[60:61]
	s_nop 0
	v_pk_fma_f32 v[48:49], v[48:49], v[58:59], v[48:49]
	v_pk_mul_f32 v[58:59], v[50:51], s[16:17] op_sel_hi:[1,0]
	v_pk_mul_f32 v[50:51], v[50:51], 0.5 op_sel_hi:[1,0]
	v_med3_f32 v58, v58, s90, v173
	v_med3_f32 v59, v59, s90, v173
	v_pk_mul_f32 v[60:61], v[58:59], v[58:59]
	s_nop 0
	v_pk_fma_f32 v[62:63], v[60:61], s[18:19], v[62:63] op_sel_hi:[1,0,0] neg_lo:[1,0,0] neg_hi:[1,0,0]
	s_nop 0
	v_pk_fma_f32 v[62:63], v[60:61], v[62:63], s[28:29] op_sel_hi:[1,1,0]
	s_nop 0
	v_pk_fma_f32 v[62:63], v[60:61], v[62:63], s[30:31] op_sel_hi:[1,1,0]
	s_nop 0
	v_pk_fma_f32 v[62:63], v[60:61], v[62:63], s[34:35] op_sel_hi:[1,1,0]
	s_nop 0
	v_pk_fma_f32 v[62:63], v[60:61], v[62:63], s[36:37] op_sel_hi:[1,1,0]
	s_nop 0
	v_pk_fma_f32 v[62:63], v[60:61], v[62:63], s[38:39] op_sel_hi:[1,1,0]
	s_nop 0
	v_pk_fma_f32 v[60:61], v[60:61], v[62:63], s[40:41] op_sel_hi:[1,1,0]
	s_nop 0
	v_pk_mul_f32 v[58:59], v[58:59], v[60:61]
	s_nop 0
	v_pk_fma_f32 v[50:51], v[50:51], v[58:59], v[50:51]
; __device__ __forceinline__ unsigned cvt_pk_bf16(float lo, float hi) { unsigned r; asm volatile("v_cvt_pk_bf16_f32 %0, %1, %2" : "=v"(r) : "v"(lo), "v"(hi)); return r; }
; __device__ __forceinline__ f32x2 gelu_pk(f32x2 v) {
;     f32x2 x = v * 0.70710678118f;
;     x.x = __builtin_amdgcn_fmed3f(x.x, -2.9f, 2.9f); x.y = __builtin_amdgcn_fmed3f(x.y, -2.9f, 2.9f);
;     const f32x2 t = x * x;
;     f32x2 p = t * (-4.953124630e-07f) + 1.987094038e-05f;
;     p = p * t + (-3.472001117e-04f); p = p * t + 3.517547622e-03f; p = p * t + (-2.333305031e-02f); p = p * t + 1.087993085e-01f; p = p * t + (-3.740358949e-01f); p = p * t + 1.128076553e+00f;
;     const f32x2 hv = v * 0.5f;
;     return hv * (x * p) + hv;
; }
;     __device__ __forceinline__ void operator()(const f32x4 (&acc)[2][2][4][2], const Unit& u, int wr, int wc, int fr, int fq) const {
;     ...
;             for (int m = 0; m < 4; ++m) { bf16_t* rowp = O + (size_t)(row0 + ai * HALF + m * 16) * ldc + col0;
;                 const float rs = rsqrtf(rsv[ai][m] * (1.f / 1024.f) + 1e-6f);
; #pragma unroll
;                 for (int bj = 0; bj < 2; ++bj) if (bj == 0 || !u.q) { f32x4 v0 = acc[ai][bj][m][0] * rs, v1 = acc[ai][bj][m][1] * rs;
;                     if (act) { f32x2 a = gelu_pk((f32x2){v0[0], v0[1]}), b = gelu_pk((f32x2){v0[2], v0[3]}), c = gelu_pk((f32x2){v1[0], v1[1]}), d = gelu_pk((f32x2){v1[2], v1[3]});
;                         v0 = (f32x4){a.x, a.y, b.x, b.y}; v1 = (f32x4){c.x, c.y, d.x, d.y}; }
;                     u32x4 w; w.x = cvt_pk_bf16(v0[0], v0[1]); w.y = cvt_pk_bf16(v0[2], v0[3]); w.z = cvt_pk_bf16(v1[0], v1[1]); w.w = cvt_pk_bf16(v1[2], v1[3]);
;                     *(u32x4*)(rowp + bj * HALF) = w; } }
.LBB0_117:
	v_cvt_pk_bf16_f32 v52, v52, v53
	v_cvt_pk_bf16_f32 v53, v54, v55
	v_fmamk_f32 v54, v149, 0x3a800000, v172
	v_mul_f32_e32 v55, 0x4b800000, v54
	v_cmp_gt_f32_e32 vcc, s87, v54
	s_nop 1
	v_cndmask_b32_e32 v54, v54, v55, vcc
	v_rsq_f32_e32 v58, v54
	v_cvt_pk_bf16_f32 v54, v48, v49
	v_cvt_pk_bf16_f32 v55, v50, v51
	global_store_dwordx4 v[56:57], v[52:55], off offset:256 sc1
	v_mul_f32_e32 v48, 0x45800000, v58
	v_cndmask_b32_e32 v48, v58, v48, vcc
	v_pk_mul_f32 v[46:47], v[46:47], v[48:49] op_sel_hi:[1,0]
	v_pk_mul_f32 v[44:45], v[44:45], v[48:49] op_sel_hi:[1,0]
	v_pk_mul_f32 v[42:43], v[42:43], v[48:49] op_sel_hi:[1,0]
	s_and_b64 vcc, exec, s[6:7]
	v_pk_mul_f32 v[50:51], v[40:41], v[48:49] op_sel_hi:[1,0]
	s_cbranch_vccnz .LBB0_119
	v_pk_mul_f32 v[40:41], v[44:45], s[16:17] op_sel_hi:[1,0]
	v_mov_b64_e32 v[54:55], s[20:21]
	v_med3_f32 v40, v40, s90, v173
	v_med3_f32 v41, v41, s90, v173
	v_pk_mul_f32 v[52:53], v[40:41], v[40:41]
	v_pk_mul_f32 v[44:45], v[44:45], 0.5 op_sel_hi:[1,0]
	v_pk_fma_f32 v[56:57], v[52:53], s[18:19], v[54:55] op_sel_hi:[1,0,0] neg_lo:[1,0,0] neg_hi:[1,0,0]
	s_nop 0
	v_pk_fma_f32 v[56:57], v[52:53], v[56:57], s[28:29] op_sel_hi:[1,1,0]
	s_nop 0
	v_pk_fma_f32 v[56:57], v[52:53], v[56:57], s[30:31] op_sel_hi:[1,1,0]
	s_nop 0
	v_pk_fma_f32 v[56:57], v[52:53], v[56:57], s[34:35] op_sel_hi:[1,1,0]
	s_nop 0
	v_pk_fma_f32 v[56:57], v[52:53], v[56:57], s[36:37] op_sel_hi:[1,1,0]
	s_nop 0
	v_pk_fma_f32 v[56:57], v[52:53], v[56:57], s[38:39] op_sel_hi:[1,1,0]
	s_nop 0
	v_pk_fma_f32 v[52:53], v[52:53], v[56:57], s[40:41] op_sel_hi:[1,1,0]
	s_nop 0
	v_pk_mul_f32 v[40:41], v[40:41], v[52:53]
	s_nop 0
	v_pk_fma_f32 v[44:45], v[44:45], v[40:41], v[44:45]
	v_pk_mul_f32 v[40:41], v[46:47], s[16:17] op_sel_hi:[1,0]
	v_pk_mul_f32 v[46:47], v[46:47], 0.5 op_sel_hi:[1,0]
	v_med3_f32 v40, v40, s90, v173
	v_med3_f32 v41, v41, s90, v173
	v_pk_mul_f32 v[52:53], v[40:41], v[40:41]
	s_nop 0
	v_pk_fma_f32 v[56:57], v[52:53], s[18:19], v[54:55] op_sel_hi:[1,0,0] neg_lo:[1,0,0] neg_hi:[1,0,0]
	s_nop 0
	v_pk_fma_f32 v[56:57], v[52:53], v[56:57], s[28:29] op_sel_hi:[1,1,0]
	s_nop 0
	v_pk_fma_f32 v[56:57], v[52:53], v[56:57], s[30:31] op_sel_hi:[1,1,0]
	s_nop 0
	v_pk_fma_f32 v[56:57], v[52:53], v[56:57], s[34:35] op_sel_hi:[1,1,0]
	s_nop 0
	v_pk_fma_f32 v[56:57], v[52:53], v[56:57], s[36:37] op_sel_hi:[1,1,0]
	s_nop 0
	v_pk_fma_f32 v[56:57], v[52:53], v[56:57], s[38:39] op_sel_hi:[1,1,0]
	s_nop 0
	v_pk_fma_f32 v[52:53], v[52:53], v[56:57], s[40:41] op_sel_hi:[1,1,0]
	s_nop 0
	v_pk_mul_f32 v[40:41], v[40:41], v[52:53]
	s_nop 0
	v_pk_fma_f32 v[46:47], v[46:47], v[40:41], v[46:47]
	v_pk_mul_f32 v[40:41], v[50:51], s[16:17] op_sel_hi:[1,0]
	v_pk_mul_f32 v[50:51], v[50:51], 0.5 op_sel_hi:[1,0]
	v_med3_f32 v40, v40, s90, v173
	v_med3_f32 v41, v41, s90, v173
	v_pk_mul_f32 v[52:53], v[40:41], v[40:41]
	s_nop 0
	v_pk_fma_f32 v[56:57], v[52:53], s[18:19], v[54:55] op_sel_hi:[1,0,0] neg_lo:[1,0,0] neg_hi:[1,0,0]
	s_nop 0
	v_pk_fma_f32 v[56:57], v[52:53], v[56:57], s[28:29] op_sel_hi:[1,1,0]
	s_nop 0
	v_pk_fma_f32 v[56:57], v[52:53], v[56:57], s[30:31] op_sel_hi:[1,1,0]
	s_nop 0
	v_pk_fma_f32 v[56:57], v[52:53], v[56:57], s[34:35] op_sel_hi:[1,1,0]
	s_nop 0
	v_pk_fma_f32 v[56:57], v[52:53], v[56:57], s[36:37] op_sel_hi:[1,1,0]
	s_nop 0
	v_pk_fma_f32 v[56:57], v[52:53], v[56:57], s[38:39] op_sel_hi:[1,1,0]
	s_nop 0
	v_pk_fma_f32 v[52:53], v[52:53], v[56:57], s[40:41] op_sel_hi:[1,1,0]
	s_nop 0
	v_pk_mul_f32 v[40:41], v[40:41], v[52:53]
	s_nop 0
	v_pk_fma_f32 v[50:51], v[50:51], v[40:41], v[50:51]
	v_pk_mul_f32 v[40:41], v[42:43], s[16:17] op_sel_hi:[1,0]
	v_pk_mul_f32 v[42:43], v[42:43], 0.5 op_sel_hi:[1,0]
	v_med3_f32 v40, v40, s90, v173
	v_med3_f32 v41, v41, s90, v173
	v_pk_mul_f32 v[52:53], v[40:41], v[40:41]
	s_nop 0
	v_pk_fma_f32 v[54:55], v[52:53], s[18:19], v[54:55] op_sel_hi:[1,0,0] neg_lo:[1,0,0] neg_hi:[1,0,0]
	s_nop 0
	v_pk_fma_f32 v[54:55], v[52:53], v[54:55], s[28:29] op_sel_hi:[1,1,0]
	s_nop 0
	v_pk_fma_f32 v[54:55], v[52:53], v[54:55], s[30:31] op_sel_hi:[1,1,0]
	s_nop 0
	v_pk_fma_f32 v[54:55], v[52:53], v[54:55], s[34:35] op_sel_hi:[1,1,0]
	s_nop 0
	v_pk_fma_f32 v[54:55], v[52:53], v[54:55], s[36:37] op_sel_hi:[1,1,0]
	s_nop 0
	v_pk_fma_f32 v[54:55], v[52:53], v[54:55], s[38:39] op_sel_hi:[1,1,0]
	s_nop 0
	v_pk_fma_f32 v[52:53], v[52:53], v[54:55], s[40:41] op_sel_hi:[1,1,0]
	s_nop 0
	v_pk_mul_f32 v[40:41], v[40:41], v[52:53]
	s_nop 0
	v_pk_fma_f32 v[42:43], v[42:43], v[40:41], v[42:43]
; __device__ __forceinline__ unsigned cvt_pk_bf16(float lo, float hi) { unsigned r; asm volatile("v_cvt_pk_bf16_f32 %0, %1, %2" : "=v"(r) : "v"(lo), "v"(hi)); return r; }
; __device__ __forceinline__ f32x2 gelu_pk(f32x2 v) {
;     f32x2 x = v * 0.70710678118f;
;     x.x = __builtin_amdgcn_fmed3f(x.x, -2.9f, 2.9f); x.y = __builtin_amdgcn_fmed3f(x.y, -2.9f, 2.9f);
;     const f32x2 t = x * x;
;     f32x2 p = t * (-4.953124630e-07f) + 1.987094038e-05f;
;     p = p * t + (-3.472001117e-04f); p = p * t + 3.517547622e-03f; p = p * t + (-2.333305031e-02f); p = p * t + 1.087993085e-01f; p = p * t + (-3.740358949e-01f); p = p * t + 1.128076553e+00f;
;     const f32x2 hv = v * 0.5f;
;     return hv * (x * p) + hv;
; }
;     __device__ __forceinline__ void operator()(const f32x4 (&acc)[2][2][4][2], const Unit& u, int wr, int wc, int fr, int fq) const {
;     ...
;             for (int m = 0; m < 4; ++m) { bf16_t* rowp = O + (size_t)(row0 + ai * HALF + m * 16) * ldc + col0;
;                 const float rs = rsqrtf(rsv[ai][m] * (1.f / 1024.f) + 1e-6f);
; #pragma unroll
;                 for (int bj = 0; bj < 2; ++bj) if (bj == 0 || !u.q) { f32x4 v0 = acc[ai][bj][m][0] * rs, v1 = acc[ai][bj][m][1] * rs;
;                     if (act) { f32x2 a = gelu_pk((f32x2){v0[0], v0[1]}), b = gelu_pk((f32x2){v0[2], v0[3]}), c = gelu_pk((f32x2){v1[0], v1[1]}), d = gelu_pk((f32x2){v1[2], v1[3]});
;                         v0 = (f32x4){a.x, a.y, b.x, b.y}; v1 = (f32x4){c.x, c.y, d.x, d.y}; }
;                     u32x4 w; w.x = cvt_pk_bf16(v0[0], v0[1]); w.y = cvt_pk_bf16(v0[2], v0[3]); w.z = cvt_pk_bf16(v1[0], v1[1]); w.w = cvt_pk_bf16(v1[2], v1[3]);
;                     *(u32x4*)(rowp + bj * HALF) = w; } }
.LBB0_119:
	v_readlane_b32 s2, v240, 12
	v_readlane_b32 s3, v240, 13
	v_mov_b32_e32 v49, v48
	v_cvt_pk_bf16_f32 v44, v44, v45
	v_cvt_pk_bf16_f32 v45, v46, v47
	v_cvt_pk_bf16_f32 v46, v50, v51
	v_cvt_pk_bf16_f32 v47, v42, v43
	s_nop 0
	v_mov_b64_e32 v[40:41], s[2:3]
	v_mad_i64_i32 v[40:41], s[2:3], v148, s91, v[40:41]
	v_mov_b32_e32 v42, v48
	v_mov_b32_e32 v43, v48
	v_lshl_add_u64 v[40:41], v[120:121], 1, v[40:41]
	v_pk_mul_f32 v[38:39], v[38:39], v[42:43]
	v_pk_mul_f32 v[36:37], v[36:37], v[48:49]
	v_pk_mul_f32 v[34:35], v[34:35], v[42:43]
	s_and_b64 vcc, exec, s[6:7]
	v_pk_mul_f32 v[32:33], v[32:33], v[48:49]
	global_store_dwordx4 v[40:41], v[44:47], off sc1
	s_cbranch_vccnz .LBB0_121
	v_pk_mul_f32 v[42:43], v[36:37], s[16:17] op_sel_hi:[1,0]
	v_mov_b64_e32 v[46:47], s[20:21]
	v_med3_f32 v42, v42, s90, v173
	v_med3_f32 v43, v43, s90, v173
	v_pk_mul_f32 v[44:45], v[42:43], v[42:43]
	v_pk_mul_f32 v[36:37], v[36:37], 0.5 op_sel_hi:[1,0]
	v_pk_fma_f32 v[48:49], v[44:45], s[18:19], v[46:47] op_sel_hi:[1,0,0] neg_lo:[1,0,0] neg_hi:[1,0,0]
	s_nop 0
	v_pk_fma_f32 v[48:49], v[44:45], v[48:49], s[28:29] op_sel_hi:[1,1,0]
	s_nop 0
	v_pk_fma_f32 v[48:49], v[44:45], v[48:49], s[30:31] op_sel_hi:[1,1,0]
	s_nop 0
	v_pk_fma_f32 v[48:49], v[44:45], v[48:49], s[34:35] op_sel_hi:[1,1,0]
	s_nop 0
	v_pk_fma_f32 v[48:49], v[44:45], v[48:49], s[36:37] op_sel_hi:[1,1,0]
	s_nop 0
	v_pk_fma_f32 v[48:49], v[44:45], v[48:49], s[38:39] op_sel_hi:[1,1,0]
	s_nop 0
	v_pk_fma_f32 v[44:45], v[44:45], v[48:49], s[40:41] op_sel_hi:[1,1,0]
	s_nop 0
	v_pk_mul_f32 v[42:43], v[42:43], v[44:45]
	s_nop 0
	v_pk_fma_f32 v[36:37], v[36:37], v[42:43], v[36:37]
	v_pk_mul_f32 v[42:43], v[38:39], s[16:17] op_sel_hi:[1,0]
	v_pk_mul_f32 v[38:39], v[38:39], 0.5 op_sel_hi:[1,0]
	v_med3_f32 v42, v42, s90, v173
	v_med3_f32 v43, v43, s90, v173
	v_pk_mul_f32 v[44:45], v[42:43], v[42:43]
	s_nop 0
	v_pk_fma_f32 v[48:49], v[44:45], s[18:19], v[46:47] op_sel_hi:[1,0,0] neg_lo:[1,0,0] neg_hi:[1,0,0]
	s_nop 0
	v_pk_fma_f32 v[48:49], v[44:45], v[48:49], s[28:29] op_sel_hi:[1,1,0]
	s_nop 0
	v_pk_fma_f32 v[48:49], v[44:45], v[48:49], s[30:31] op_sel_hi:[1,1,0]
	s_nop 0
	v_pk_fma_f32 v[48:49], v[44:45], v[48:49], s[34:35] op_sel_hi:[1,1,0]
	s_nop 0
	v_pk_fma_f32 v[48:49], v[44:45], v[48:49], s[36:37] op_sel_hi:[1,1,0]
	s_nop 0
	v_pk_fma_f32 v[48:49], v[44:45], v[48:49], s[38:39] op_sel_hi:[1,1,0]
	s_nop 0
	v_pk_fma_f32 v[44:45], v[44:45], v[48:49], s[40:41] op_sel_hi:[1,1,0]
	s_nop 0
	v_pk_mul_f32 v[42:43], v[42:43], v[44:45]
	s_nop 0
	v_pk_fma_f32 v[38:39], v[38:39], v[42:43], v[38:39]
	v_pk_mul_f32 v[42:43], v[32:33], s[16:17] op_sel_hi:[1,0]
	v_pk_mul_f32 v[32:33], v[32:33], 0.5 op_sel_hi:[1,0]
	v_med3_f32 v42, v42, s90, v173
	v_med3_f32 v43, v43, s90, v173
	v_pk_mul_f32 v[44:45], v[42:43], v[42:43]
	s_nop 0
	v_pk_fma_f32 v[48:49], v[44:45], s[18:19], v[46:47] op_sel_hi:[1,0,0] neg_lo:[1,0,0] neg_hi:[1,0,0]
	s_nop 0
	v_pk_fma_f32 v[48:49], v[44:45], v[48:49], s[28:29] op_sel_hi:[1,1,0]
	s_nop 0
	v_pk_fma_f32 v[48:49], v[44:45], v[48:49], s[30:31] op_sel_hi:[1,1,0]
	s_nop 0
	v_pk_fma_f32 v[48:49], v[44:45], v[48:49], s[34:35] op_sel_hi:[1,1,0]
	s_nop 0
	v_pk_fma_f32 v[48:49], v[44:45], v[48:49], s[36:37] op_sel_hi:[1,1,0]
	s_nop 0
	v_pk_fma_f32 v[48:49], v[44:45], v[48:49], s[38:39] op_sel_hi:[1,1,0]
	s_nop 0
	v_pk_fma_f32 v[44:45], v[44:45], v[48:49], s[40:41] op_sel_hi:[1,1,0]
	s_nop 0
	v_pk_mul_f32 v[42:43], v[42:43], v[44:45]
	s_nop 0
	v_pk_fma_f32 v[32:33], v[32:33], v[42:43], v[32:33]
	v_pk_mul_f32 v[42:43], v[34:35], s[16:17] op_sel_hi:[1,0]
	v_pk_mul_f32 v[34:35], v[34:35], 0.5 op_sel_hi:[1,0]
	v_med3_f32 v42, v42, s90, v173
	v_med3_f32 v43, v43, s90, v173
	v_pk_mul_f32 v[44:45], v[42:43], v[42:43]
	s_nop 0
	v_pk_fma_f32 v[46:47], v[44:45], s[18:19], v[46:47] op_sel_hi:[1,0,0] neg_lo:[1,0,0] neg_hi:[1,0,0]
	s_nop 0
	v_pk_fma_f32 v[46:47], v[44:45], v[46:47], s[28:29] op_sel_hi:[1,1,0]
	s_nop 0
	v_pk_fma_f32 v[46:47], v[44:45], v[46:47], s[30:31] op_sel_hi:[1,1,0]
	s_nop 0
	v_pk_fma_f32 v[46:47], v[44:45], v[46:47], s[34:35] op_sel_hi:[1,1,0]
	s_nop 0
	v_pk_fma_f32 v[46:47], v[44:45], v[46:47], s[36:37] op_sel_hi:[1,1,0]
	s_nop 0
	v_pk_fma_f32 v[46:47], v[44:45], v[46:47], s[38:39] op_sel_hi:[1,1,0]
	s_nop 0
	v_pk_fma_f32 v[44:45], v[44:45], v[46:47], s[40:41] op_sel_hi:[1,1,0]
	s_nop 0
	v_pk_mul_f32 v[42:43], v[42:43], v[44:45]
	s_nop 0
	v_pk_fma_f32 v[34:35], v[34:35], v[42:43], v[34:35]
; __device__ __forceinline__ unsigned cvt_pk_bf16(float lo, float hi) { unsigned r; asm volatile("v_cvt_pk_bf16_f32 %0, %1, %2" : "=v"(r) : "v"(lo), "v"(hi)); return r; }
; __device__ __forceinline__ f32x2 gelu_pk(f32x2 v) {
;     f32x2 x = v * 0.70710678118f;
;     x.x = __builtin_amdgcn_fmed3f(x.x, -2.9f, 2.9f); x.y = __builtin_amdgcn_fmed3f(x.y, -2.9f, 2.9f);
;     const f32x2 t = x * x;
;     f32x2 p = t * (-4.953124630e-07f) + 1.987094038e-05f;
;     p = p * t + (-3.472001117e-04f); p = p * t + 3.517547622e-03f; p = p * t + (-2.333305031e-02f); p = p * t + 1.087993085e-01f; p = p * t + (-3.740358949e-01f); p = p * t + 1.128076553e+00f;
;     const f32x2 hv = v * 0.5f;
;     return hv * (x * p) + hv;
; }
;     __device__ __forceinline__ void operator()(const f32x4 (&acc)[2][2][4][2], const Unit& u, int wr, int wc, int fr, int fq) const {
;     ...
;             for (int m = 0; m < 4; ++m) { bf16_t* rowp = O + (size_t)(row0 + ai * HALF + m * 16) * ldc + col0;
;                 const float rs = rsqrtf(rsv[ai][m] * (1.f / 1024.f) + 1e-6f);
; #pragma unroll
;                 for (int bj = 0; bj < 2; ++bj) if (bj == 0 || !u.q) { f32x4 v0 = acc[ai][bj][m][0] * rs, v1 = acc[ai][bj][m][1] * rs;
;                     if (act) { f32x2 a = gelu_pk((f32x2){v0[0], v0[1]}), b = gelu_pk((f32x2){v0[2], v0[3]}), c = gelu_pk((f32x2){v1[0], v1[1]}), d = gelu_pk((f32x2){v1[2], v1[3]});
;                         v0 = (f32x4){a.x, a.y, b.x, b.y}; v1 = (f32x4){c.x, c.y, d.x, d.y}; }
;                     u32x4 w; w.x = cvt_pk_bf16(v0[0], v0[1]); w.y = cvt_pk_bf16(v0[2], v0[3]); w.z = cvt_pk_bf16(v1[0], v1[1]); w.w = cvt_pk_bf16(v1[2], v1[3]);
;                     *(u32x4*)(rowp + bj * HALF) = w; } }
.LBB0_121:
	v_cvt_pk_bf16_f32 v36, v36, v37
	v_cvt_pk_bf16_f32 v37, v38, v39
	v_fmamk_f32 v38, v147, 0x3a800000, v172
	v_mul_f32_e32 v39, 0x4b800000, v38
	v_cmp_gt_f32_e32 vcc, s87, v38
	s_nop 1
	v_cndmask_b32_e32 v38, v38, v39, vcc
	v_rsq_f32_e32 v42, v38
	v_cvt_pk_bf16_f32 v38, v32, v33
	v_cvt_pk_bf16_f32 v39, v34, v35
	global_store_dwordx4 v[40:41], v[36:39], off offset:256 sc1
	v_mul_f32_e32 v32, 0x45800000, v42
	v_cndmask_b32_e32 v32, v42, v32, vcc
	v_pk_mul_f32 v[30:31], v[30:31], v[32:33] op_sel_hi:[1,0]
	v_pk_mul_f32 v[28:29], v[28:29], v[32:33] op_sel_hi:[1,0]
	v_pk_mul_f32 v[26:27], v[26:27], v[32:33] op_sel_hi:[1,0]
	s_and_b64 vcc, exec, s[6:7]
	v_pk_mul_f32 v[34:35], v[24:25], v[32:33] op_sel_hi:[1,0]
	s_cbranch_vccnz .LBB0_123
	v_pk_mul_f32 v[24:25], v[28:29], s[16:17] op_sel_hi:[1,0]
	v_mov_b64_e32 v[38:39], s[20:21]
	v_med3_f32 v24, v24, s90, v173
	v_med3_f32 v25, v25, s90, v173
	v_pk_mul_f32 v[36:37], v[24:25], v[24:25]
	v_pk_mul_f32 v[28:29], v[28:29], 0.5 op_sel_hi:[1,0]
	v_pk_fma_f32 v[40:41], v[36:37], s[18:19], v[38:39] op_sel_hi:[1,0,0] neg_lo:[1,0,0] neg_hi:[1,0,0]
	s_nop 0
	v_pk_fma_f32 v[40:41], v[36:37], v[40:41], s[28:29] op_sel_hi:[1,1,0]
	s_nop 0
	v_pk_fma_f32 v[40:41], v[36:37], v[40:41], s[30:31] op_sel_hi:[1,1,0]
	s_nop 0
	v_pk_fma_f32 v[40:41], v[36:37], v[40:41], s[34:35] op_sel_hi:[1,1,0]
	s_nop 0
	v_pk_fma_f32 v[40:41], v[36:37], v[40:41], s[36:37] op_sel_hi:[1,1,0]
	s_nop 0
	v_pk_fma_f32 v[40:41], v[36:37], v[40:41], s[38:39] op_sel_hi:[1,1,0]
	s_nop 0
	v_pk_fma_f32 v[36:37], v[36:37], v[40:41], s[40:41] op_sel_hi:[1,1,0]
	s_nop 0
	v_pk_mul_f32 v[24:25], v[24:25], v[36:37]
	s_nop 0
	v_pk_fma_f32 v[28:29], v[28:29], v[24:25], v[28:29]
	v_pk_mul_f32 v[24:25], v[30:31], s[16:17] op_sel_hi:[1,0]
	v_pk_mul_f32 v[30:31], v[30:31], 0.5 op_sel_hi:[1,0]
	v_med3_f32 v24, v24, s90, v173
	v_med3_f32 v25, v25, s90, v173
	v_pk_mul_f32 v[36:37], v[24:25], v[24:25]
	s_nop 0
	v_pk_fma_f32 v[40:41], v[36:37], s[18:19], v[38:39] op_sel_hi:[1,0,0] neg_lo:[1,0,0] neg_hi:[1,0,0]
	s_nop 0
	v_pk_fma_f32 v[40:41], v[36:37], v[40:41], s[28:29] op_sel_hi:[1,1,0]
	s_nop 0
	v_pk_fma_f32 v[40:41], v[36:37], v[40:41], s[30:31] op_sel_hi:[1,1,0]
	s_nop 0
	v_pk_fma_f32 v[40:41], v[36:37], v[40:41], s[34:35] op_sel_hi:[1,1,0]
	s_nop 0
	v_pk_fma_f32 v[40:41], v[36:37], v[40:41], s[36:37] op_sel_hi:[1,1,0]
	s_nop 0
	v_pk_fma_f32 v[40:41], v[36:37], v[40:41], s[38:39] op_sel_hi:[1,1,0]
	s_nop 0
	v_pk_fma_f32 v[36:37], v[36:37], v[40:41], s[40:41] op_sel_hi:[1,1,0]
	s_nop 0
	v_pk_mul_f32 v[24:25], v[24:25], v[36:37]
	s_nop 0
	v_pk_fma_f32 v[30:31], v[30:31], v[24:25], v[30:31]
	v_pk_mul_f32 v[24:25], v[34:35], s[16:17] op_sel_hi:[1,0]
	v_pk_mul_f32 v[34:35], v[34:35], 0.5 op_sel_hi:[1,0]
	v_med3_f32 v24, v24, s90, v173
	v_med3_f32 v25, v25, s90, v173
	v_pk_mul_f32 v[36:37], v[24:25], v[24:25]
	s_nop 0
	v_pk_fma_f32 v[40:41], v[36:37], s[18:19], v[38:39] op_sel_hi:[1,0,0] neg_lo:[1,0,0] neg_hi:[1,0,0]
	s_nop 0
	v_pk_fma_f32 v[40:41], v[36:37], v[40:41], s[28:29] op_sel_hi:[1,1,0]
	s_nop 0
	v_pk_fma_f32 v[40:41], v[36:37], v[40:41], s[30:31] op_sel_hi:[1,1,0]
	s_nop 0
	v_pk_fma_f32 v[40:41], v[36:37], v[40:41], s[34:35] op_sel_hi:[1,1,0]
	s_nop 0
	v_pk_fma_f32 v[40:41], v[36:37], v[40:41], s[36:37] op_sel_hi:[1,1,0]
	s_nop 0
	v_pk_fma_f32 v[40:41], v[36:37], v[40:41], s[38:39] op_sel_hi:[1,1,0]
	s_nop 0
	v_pk_fma_f32 v[36:37], v[36:37], v[40:41], s[40:41] op_sel_hi:[1,1,0]
	s_nop 0
	v_pk_mul_f32 v[24:25], v[24:25], v[36:37]
	s_nop 0
	v_pk_fma_f32 v[34:35], v[34:35], v[24:25], v[34:35]
	v_pk_mul_f32 v[24:25], v[26:27], s[16:17] op_sel_hi:[1,0]
	v_pk_mul_f32 v[26:27], v[26:27], 0.5 op_sel_hi:[1,0]
	v_med3_f32 v24, v24, s90, v173
	v_med3_f32 v25, v25, s90, v173
	v_pk_mul_f32 v[36:37], v[24:25], v[24:25]
	s_nop 0
	v_pk_fma_f32 v[38:39], v[36:37], s[18:19], v[38:39] op_sel_hi:[1,0,0] neg_lo:[1,0,0] neg_hi:[1,0,0]
	s_nop 0
	v_pk_fma_f32 v[38:39], v[36:37], v[38:39], s[28:29] op_sel_hi:[1,1,0]
	s_nop 0
	v_pk_fma_f32 v[38:39], v[36:37], v[38:39], s[30:31] op_sel_hi:[1,1,0]
	s_nop 0
	v_pk_fma_f32 v[38:39], v[36:37], v[38:39], s[34:35] op_sel_hi:[1,1,0]
	s_nop 0
	v_pk_fma_f32 v[38:39], v[36:37], v[38:39], s[36:37] op_sel_hi:[1,1,0]
	s_nop 0
	v_pk_fma_f32 v[38:39], v[36:37], v[38:39], s[38:39] op_sel_hi:[1,1,0]
	s_nop 0
	v_pk_fma_f32 v[36:37], v[36:37], v[38:39], s[40:41] op_sel_hi:[1,1,0]
	s_nop 0
	v_pk_mul_f32 v[24:25], v[24:25], v[36:37]
	s_nop 0
	v_pk_fma_f32 v[26:27], v[26:27], v[24:25], v[26:27]
; __device__ __forceinline__ unsigned cvt_pk_bf16(float lo, float hi) { unsigned r; asm volatile("v_cvt_pk_bf16_f32 %0, %1, %2" : "=v"(r) : "v"(lo), "v"(hi)); return r; }
; __device__ __forceinline__ f32x2 gelu_pk(f32x2 v) {
;     f32x2 x = v * 0.70710678118f;
;     x.x = __builtin_amdgcn_fmed3f(x.x, -2.9f, 2.9f); x.y = __builtin_amdgcn_fmed3f(x.y, -2.9f, 2.9f);
;     const f32x2 t = x * x;
;     f32x2 p = t * (-4.953124630e-07f) + 1.987094038e-05f;
;     p = p * t + (-3.472001117e-04f); p = p * t + 3.517547622e-03f; p = p * t + (-2.333305031e-02f); p = p * t + 1.087993085e-01f; p = p * t + (-3.740358949e-01f); p = p * t + 1.128076553e+00f;
;     const f32x2 hv = v * 0.5f;
;     return hv * (x * p) + hv;
; }
;     __device__ __forceinline__ void operator()(const f32x4 (&acc)[2][2][4][2], const Unit& u, int wr, int wc, int fr, int fq) const {
;     ...
;             for (int m = 0; m < 4; ++m) { bf16_t* rowp = O + (size_t)(row0 + ai * HALF + m * 16) * ldc + col0;
;                 const float rs = rsqrtf(rsv[ai][m] * (1.f / 1024.f) + 1e-6f);
; #pragma unroll
;                 for (int bj = 0; bj < 2; ++bj) if (bj == 0 || !u.q) { f32x4 v0 = acc[ai][bj][m][0] * rs, v1 = acc[ai][bj][m][1] * rs;
;                     if (act) { f32x2 a = gelu_pk((f32x2){v0[0], v0[1]}), b = gelu_pk((f32x2){v0[2], v0[3]}), c = gelu_pk((f32x2){v1[0], v1[1]}), d = gelu_pk((f32x2){v1[2], v1[3]});
;                         v0 = (f32x4){a.x, a.y, b.x, b.y}; v1 = (f32x4){c.x, c.y, d.x, d.y}; }
;                     u32x4 w; w.x = cvt_pk_bf16(v0[0], v0[1]); w.y = cvt_pk_bf16(v0[2], v0[3]); w.z = cvt_pk_bf16(v1[0], v1[1]); w.w = cvt_pk_bf16(v1[2], v1[3]);
;                     *(u32x4*)(rowp + bj * HALF) = w; } }
.LBB0_123:
	v_readlane_b32 s2, v240, 12
	v_readlane_b32 s3, v240, 13
	v_mov_b32_e32 v33, v32
	v_cvt_pk_bf16_f32 v28, v28, v29
	v_cvt_pk_bf16_f32 v29, v30, v31
	v_cvt_pk_bf16_f32 v30, v34, v35
	v_cvt_pk_bf16_f32 v31, v26, v27
	s_nop 0
	v_mov_b64_e32 v[24:25], s[2:3]
	v_mad_i64_i32 v[24:25], s[2:3], v146, s91, v[24:25]
	v_mov_b32_e32 v26, v32
	v_mov_b32_e32 v27, v32
	v_lshl_add_u64 v[24:25], v[120:121], 1, v[24:25]
	v_pk_mul_f32 v[22:23], v[22:23], v[26:27]
	v_pk_mul_f32 v[20:21], v[20:21], v[32:33]
	v_pk_mul_f32 v[18:19], v[18:19], v[26:27]
	s_and_b64 vcc, exec, s[6:7]
	v_pk_mul_f32 v[16:17], v[16:17], v[32:33]
	global_store_dwordx4 v[24:25], v[28:31], off sc1
	s_cbranch_vccnz .LBB0_125
	v_pk_mul_f32 v[26:27], v[20:21], s[16:17] op_sel_hi:[1,0]
	v_mov_b64_e32 v[30:31], s[20:21]
	v_med3_f32 v26, v26, s90, v173
	v_med3_f32 v27, v27, s90, v173
	v_pk_mul_f32 v[28:29], v[26:27], v[26:27]
	v_pk_mul_f32 v[20:21], v[20:21], 0.5 op_sel_hi:[1,0]
	v_pk_fma_f32 v[32:33], v[28:29], s[18:19], v[30:31] op_sel_hi:[1,0,0] neg_lo:[1,0,0] neg_hi:[1,0,0]
	s_nop 0
	v_pk_fma_f32 v[32:33], v[28:29], v[32:33], s[28:29] op_sel_hi:[1,1,0]
	s_nop 0
	v_pk_fma_f32 v[32:33], v[28:29], v[32:33], s[30:31] op_sel_hi:[1,1,0]
	s_nop 0
	v_pk_fma_f32 v[32:33], v[28:29], v[32:33], s[34:35] op_sel_hi:[1,1,0]
	s_nop 0
	v_pk_fma_f32 v[32:33], v[28:29], v[32:33], s[36:37] op_sel_hi:[1,1,0]
	s_nop 0
	v_pk_fma_f32 v[32:33], v[28:29], v[32:33], s[38:39] op_sel_hi:[1,1,0]
	s_nop 0
	v_pk_fma_f32 v[28:29], v[28:29], v[32:33], s[40:41] op_sel_hi:[1,1,0]
	s_nop 0
	v_pk_mul_f32 v[26:27], v[26:27], v[28:29]
	s_nop 0
	v_pk_fma_f32 v[20:21], v[20:21], v[26:27], v[20:21]
	v_pk_mul_f32 v[26:27], v[22:23], s[16:17] op_sel_hi:[1,0]
	v_pk_mul_f32 v[22:23], v[22:23], 0.5 op_sel_hi:[1,0]
	v_med3_f32 v26, v26, s90, v173
	v_med3_f32 v27, v27, s90, v173
	v_pk_mul_f32 v[28:29], v[26:27], v[26:27]
	s_nop 0
	v_pk_fma_f32 v[32:33], v[28:29], s[18:19], v[30:31] op_sel_hi:[1,0,0] neg_lo:[1,0,0] neg_hi:[1,0,0]
	s_nop 0
	v_pk_fma_f32 v[32:33], v[28:29], v[32:33], s[28:29] op_sel_hi:[1,1,0]
	s_nop 0
	v_pk_fma_f32 v[32:33], v[28:29], v[32:33], s[30:31] op_sel_hi:[1,1,0]
	s_nop 0
	v_pk_fma_f32 v[32:33], v[28:29], v[32:33], s[34:35] op_sel_hi:[1,1,0]
	s_nop 0
	v_pk_fma_f32 v[32:33], v[28:29], v[32:33], s[36:37] op_sel_hi:[1,1,0]
	s_nop 0
	v_pk_fma_f32 v[32:33], v[28:29], v[32:33], s[38:39] op_sel_hi:[1,1,0]
	s_nop 0
	v_pk_fma_f32 v[28:29], v[28:29], v[32:33], s[40:41] op_sel_hi:[1,1,0]
	s_nop 0
	v_pk_mul_f32 v[26:27], v[26:27], v[28:29]
	s_nop 0
	v_pk_fma_f32 v[22:23], v[22:23], v[26:27], v[22:23]
	v_pk_mul_f32 v[26:27], v[16:17], s[16:17] op_sel_hi:[1,0]
	v_pk_mul_f32 v[16:17], v[16:17], 0.5 op_sel_hi:[1,0]
	v_med3_f32 v26, v26, s90, v173
	v_med3_f32 v27, v27, s90, v173
	v_pk_mul_f32 v[28:29], v[26:27], v[26:27]
	s_nop 0
	v_pk_fma_f32 v[32:33], v[28:29], s[18:19], v[30:31] op_sel_hi:[1,0,0] neg_lo:[1,0,0] neg_hi:[1,0,0]
	s_nop 0
	v_pk_fma_f32 v[32:33], v[28:29], v[32:33], s[28:29] op_sel_hi:[1,1,0]
	s_nop 0
	v_pk_fma_f32 v[32:33], v[28:29], v[32:33], s[30:31] op_sel_hi:[1,1,0]
	s_nop 0
	v_pk_fma_f32 v[32:33], v[28:29], v[32:33], s[34:35] op_sel_hi:[1,1,0]
	s_nop 0
	v_pk_fma_f32 v[32:33], v[28:29], v[32:33], s[36:37] op_sel_hi:[1,1,0]
	s_nop 0
	v_pk_fma_f32 v[32:33], v[28:29], v[32:33], s[38:39] op_sel_hi:[1,1,0]
	s_nop 0
	v_pk_fma_f32 v[28:29], v[28:29], v[32:33], s[40:41] op_sel_hi:[1,1,0]
	s_nop 0
	v_pk_mul_f32 v[26:27], v[26:27], v[28:29]
	s_nop 0
	v_pk_fma_f32 v[16:17], v[16:17], v[26:27], v[16:17]
	v_pk_mul_f32 v[26:27], v[18:19], s[16:17] op_sel_hi:[1,0]
	v_pk_mul_f32 v[18:19], v[18:19], 0.5 op_sel_hi:[1,0]
	v_med3_f32 v26, v26, s90, v173
	v_med3_f32 v27, v27, s90, v173
	v_pk_mul_f32 v[28:29], v[26:27], v[26:27]
	s_nop 0
	v_pk_fma_f32 v[30:31], v[28:29], s[18:19], v[30:31] op_sel_hi:[1,0,0] neg_lo:[1,0,0] neg_hi:[1,0,0]
	s_nop 0
	v_pk_fma_f32 v[30:31], v[28:29], v[30:31], s[28:29] op_sel_hi:[1,1,0]
	s_nop 0
	v_pk_fma_f32 v[30:31], v[28:29], v[30:31], s[30:31] op_sel_hi:[1,1,0]
	s_nop 0
	v_pk_fma_f32 v[30:31], v[28:29], v[30:31], s[34:35] op_sel_hi:[1,1,0]
	s_nop 0
	v_pk_fma_f32 v[30:31], v[28:29], v[30:31], s[36:37] op_sel_hi:[1,1,0]
	s_nop 0
	v_pk_fma_f32 v[30:31], v[28:29], v[30:31], s[38:39] op_sel_hi:[1,1,0]
	s_nop 0
	v_pk_fma_f32 v[28:29], v[28:29], v[30:31], s[40:41] op_sel_hi:[1,1,0]
	s_nop 0
	v_pk_mul_f32 v[26:27], v[26:27], v[28:29]
	s_nop 0
	v_pk_fma_f32 v[18:19], v[18:19], v[26:27], v[18:19]
; __device__ __forceinline__ unsigned cvt_pk_bf16(float lo, float hi) { unsigned r; asm volatile("v_cvt_pk_bf16_f32 %0, %1, %2" : "=v"(r) : "v"(lo), "v"(hi)); return r; }
; __device__ __forceinline__ f32x2 gelu_pk(f32x2 v) {
;     f32x2 x = v * 0.70710678118f;
;     x.x = __builtin_amdgcn_fmed3f(x.x, -2.9f, 2.9f); x.y = __builtin_amdgcn_fmed3f(x.y, -2.9f, 2.9f);
;     const f32x2 t = x * x;
;     f32x2 p = t * (-4.953124630e-07f) + 1.987094038e-05f;
;     p = p * t + (-3.472001117e-04f); p = p * t + 3.517547622e-03f; p = p * t + (-2.333305031e-02f); p = p * t + 1.087993085e-01f; p = p * t + (-3.740358949e-01f); p = p * t + 1.128076553e+00f;
;     const f32x2 hv = v * 0.5f;
;     return hv * (x * p) + hv;
; }
;     __device__ __forceinline__ void operator()(const f32x4 (&acc)[2][2][4][2], const Unit& u, int wr, int wc, int fr, int fq) const {
;     ...
;             for (int m = 0; m < 4; ++m) { bf16_t* rowp = O + (size_t)(row0 + ai * HALF + m * 16) * ldc + col0;
;                 const float rs = rsqrtf(rsv[ai][m] * (1.f / 1024.f) + 1e-6f);
; #pragma unroll
;                 for (int bj = 0; bj < 2; ++bj) if (bj == 0 || !u.q) { f32x4 v0 = acc[ai][bj][m][0] * rs, v1 = acc[ai][bj][m][1] * rs;
;                     if (act) { f32x2 a = gelu_pk((f32x2){v0[0], v0[1]}), b = gelu_pk((f32x2){v0[2], v0[3]}), c = gelu_pk((f32x2){v1[0], v1[1]}), d = gelu_pk((f32x2){v1[2], v1[3]});
;                         v0 = (f32x4){a.x, a.y, b.x, b.y}; v1 = (f32x4){c.x, c.y, d.x, d.y}; }
;                     u32x4 w; w.x = cvt_pk_bf16(v0[0], v0[1]); w.y = cvt_pk_bf16(v0[2], v0[3]); w.z = cvt_pk_bf16(v1[0], v1[1]); w.w = cvt_pk_bf16(v1[2], v1[3]);
;                     *(u32x4*)(rowp + bj * HALF) = w; } }
.LBB0_125:
	v_cvt_pk_bf16_f32 v20, v20, v21
	v_cvt_pk_bf16_f32 v21, v22, v23
	v_fmamk_f32 v22, v145, 0x3a800000, v172
	v_mul_f32_e32 v23, 0x4b800000, v22
	v_cmp_gt_f32_e32 vcc, s87, v22
	s_nop 1
	v_cndmask_b32_e32 v22, v22, v23, vcc
	v_rsq_f32_e32 v26, v22
	v_cvt_pk_bf16_f32 v22, v16, v17
	v_cvt_pk_bf16_f32 v23, v18, v19
	global_store_dwordx4 v[24:25], v[20:23], off offset:256 sc1
	v_mul_f32_e32 v16, 0x45800000, v26
	v_cndmask_b32_e32 v16, v26, v16, vcc
	v_pk_mul_f32 v[14:15], v[14:15], v[16:17] op_sel_hi:[1,0]
	v_pk_mul_f32 v[12:13], v[12:13], v[16:17] op_sel_hi:[1,0]
	v_pk_mul_f32 v[10:11], v[10:11], v[16:17] op_sel_hi:[1,0]
	s_and_b64 vcc, exec, s[6:7]
	v_pk_mul_f32 v[18:19], v[8:9], v[16:17] op_sel_hi:[1,0]
	s_cbranch_vccnz .LBB0_127
	v_pk_mul_f32 v[8:9], v[12:13], s[16:17] op_sel_hi:[1,0]
	v_mov_b64_e32 v[22:23], s[20:21]
	v_med3_f32 v8, v8, s90, v173
	v_med3_f32 v9, v9, s90, v173
	v_pk_mul_f32 v[20:21], v[8:9], v[8:9]
	v_pk_mul_f32 v[12:13], v[12:13], 0.5 op_sel_hi:[1,0]
	v_pk_fma_f32 v[24:25], v[20:21], s[18:19], v[22:23] op_sel_hi:[1,0,0] neg_lo:[1,0,0] neg_hi:[1,0,0]
	s_nop 0
	v_pk_fma_f32 v[24:25], v[20:21], v[24:25], s[28:29] op_sel_hi:[1,1,0]
	s_nop 0
	v_pk_fma_f32 v[24:25], v[20:21], v[24:25], s[30:31] op_sel_hi:[1,1,0]
	s_nop 0
	v_pk_fma_f32 v[24:25], v[20:21], v[24:25], s[34:35] op_sel_hi:[1,1,0]
	s_nop 0
	v_pk_fma_f32 v[24:25], v[20:21], v[24:25], s[36:37] op_sel_hi:[1,1,0]
	s_nop 0
	v_pk_fma_f32 v[24:25], v[20:21], v[24:25], s[38:39] op_sel_hi:[1,1,0]
	s_nop 0
	v_pk_fma_f32 v[20:21], v[20:21], v[24:25], s[40:41] op_sel_hi:[1,1,0]
	s_nop 0
	v_pk_mul_f32 v[8:9], v[8:9], v[20:21]
	s_nop 0
	v_pk_fma_f32 v[12:13], v[12:13], v[8:9], v[12:13]
	v_pk_mul_f32 v[8:9], v[14:15], s[16:17] op_sel_hi:[1,0]
	v_pk_mul_f32 v[14:15], v[14:15], 0.5 op_sel_hi:[1,0]
	v_med3_f32 v8, v8, s90, v173
	v_med3_f32 v9, v9, s90, v173
	v_pk_mul_f32 v[20:21], v[8:9], v[8:9]
	s_nop 0
	v_pk_fma_f32 v[24:25], v[20:21], s[18:19], v[22:23] op_sel_hi:[1,0,0] neg_lo:[1,0,0] neg_hi:[1,0,0]
	s_nop 0
	v_pk_fma_f32 v[24:25], v[20:21], v[24:25], s[28:29] op_sel_hi:[1,1,0]
	s_nop 0
	v_pk_fma_f32 v[24:25], v[20:21], v[24:25], s[30:31] op_sel_hi:[1,1,0]
	s_nop 0
	v_pk_fma_f32 v[24:25], v[20:21], v[24:25], s[34:35] op_sel_hi:[1,1,0]
	s_nop 0
	v_pk_fma_f32 v[24:25], v[20:21], v[24:25], s[36:37] op_sel_hi:[1,1,0]
	s_nop 0
	v_pk_fma_f32 v[24:25], v[20:21], v[24:25], s[38:39] op_sel_hi:[1,1,0]
	s_nop 0
	v_pk_fma_f32 v[20:21], v[20:21], v[24:25], s[40:41] op_sel_hi:[1,1,0]
	s_nop 0
	v_pk_mul_f32 v[8:9], v[8:9], v[20:21]
	s_nop 0
	v_pk_fma_f32 v[14:15], v[14:15], v[8:9], v[14:15]
	v_pk_mul_f32 v[8:9], v[18:19], s[16:17] op_sel_hi:[1,0]
	v_pk_mul_f32 v[18:19], v[18:19], 0.5 op_sel_hi:[1,0]
	v_med3_f32 v8, v8, s90, v173
	v_med3_f32 v9, v9, s90, v173
	v_pk_mul_f32 v[20:21], v[8:9], v[8:9]
	s_nop 0
	v_pk_fma_f32 v[24:25], v[20:21], s[18:19], v[22:23] op_sel_hi:[1,0,0] neg_lo:[1,0,0] neg_hi:[1,0,0]
	s_nop 0
	v_pk_fma_f32 v[24:25], v[20:21], v[24:25], s[28:29] op_sel_hi:[1,1,0]
	s_nop 0
	v_pk_fma_f32 v[24:25], v[20:21], v[24:25], s[30:31] op_sel_hi:[1,1,0]
	s_nop 0
	v_pk_fma_f32 v[24:25], v[20:21], v[24:25], s[34:35] op_sel_hi:[1,1,0]
	s_nop 0
	v_pk_fma_f32 v[24:25], v[20:21], v[24:25], s[36:37] op_sel_hi:[1,1,0]
	s_nop 0
	v_pk_fma_f32 v[24:25], v[20:21], v[24:25], s[38:39] op_sel_hi:[1,1,0]
	s_nop 0
	v_pk_fma_f32 v[20:21], v[20:21], v[24:25], s[40:41] op_sel_hi:[1,1,0]
	s_nop 0
	v_pk_mul_f32 v[8:9], v[8:9], v[20:21]
	s_nop 0
	v_pk_fma_f32 v[18:19], v[18:19], v[8:9], v[18:19]
	v_pk_mul_f32 v[8:9], v[10:11], s[16:17] op_sel_hi:[1,0]
	v_pk_mul_f32 v[10:11], v[10:11], 0.5 op_sel_hi:[1,0]
	v_med3_f32 v8, v8, s90, v173
	v_med3_f32 v9, v9, s90, v173
	v_pk_mul_f32 v[20:21], v[8:9], v[8:9]
	s_nop 0
	v_pk_fma_f32 v[22:23], v[20:21], s[18:19], v[22:23] op_sel_hi:[1,0,0] neg_lo:[1,0,0] neg_hi:[1,0,0]
	s_nop 0
	v_pk_fma_f32 v[22:23], v[20:21], v[22:23], s[28:29] op_sel_hi:[1,1,0]
	s_nop 0
	v_pk_fma_f32 v[22:23], v[20:21], v[22:23], s[30:31] op_sel_hi:[1,1,0]
	s_nop 0
	v_pk_fma_f32 v[22:23], v[20:21], v[22:23], s[34:35] op_sel_hi:[1,1,0]
	s_nop 0
	v_pk_fma_f32 v[22:23], v[20:21], v[22:23], s[36:37] op_sel_hi:[1,1,0]
	s_nop 0
	v_pk_fma_f32 v[22:23], v[20:21], v[22:23], s[38:39] op_sel_hi:[1,1,0]
	s_nop 0
	v_pk_fma_f32 v[20:21], v[20:21], v[22:23], s[40:41] op_sel_hi:[1,1,0]
	s_nop 0
	v_pk_mul_f32 v[8:9], v[8:9], v[20:21]
	s_nop 0
	v_pk_fma_f32 v[10:11], v[10:11], v[8:9], v[10:11]
; __device__ __forceinline__ unsigned cvt_pk_bf16(float lo, float hi) { unsigned r; asm volatile("v_cvt_pk_bf16_f32 %0, %1, %2" : "=v"(r) : "v"(lo), "v"(hi)); return r; }
; #define PG8_BAR __builtin_amdgcn_s_barrier()
;     __device__ __forceinline__ void operator()(const f32x4 (&acc)[2][2][4][2], const Unit& u, int wr, int wc, int fr, int fq) const {
;     ...
;             for (int m = 0; m < 4; ++m) { bf16_t* rowp = O + (size_t)(row0 + ai * HALF + m * 16) * ldc + col0;
;                 const float rs = rsqrtf(rsv[ai][m] * (1.f / 1024.f) + 1e-6f);
; #pragma unroll
;                 for (int bj = 0; bj < 2; ++bj) if (bj == 0 || !u.q) { f32x4 v0 = acc[ai][bj][m][0] * rs, v1 = acc[ai][bj][m][1] * rs;
;                     if (act) { f32x2 a = gelu_pk((f32x2){v0[0], v0[1]}), b = gelu_pk((f32x2){v0[2], v0[3]}), c = gelu_pk((f32x2){v1[0], v1[1]}), d = gelu_pk((f32x2){v1[2], v1[3]});
;                         v0 = (f32x4){a.x, a.y, b.x, b.y}; v1 = (f32x4){c.x, c.y, d.x, d.y}; }
;                     u32x4 w; w.x = cvt_pk_bf16(v0[0], v0[1]); w.y = cvt_pk_bf16(v0[2], v0[3]); w.z = cvt_pk_bf16(v1[0], v1[1]); w.w = cvt_pk_bf16(v1[2], v1[3]);
;                     *(u32x4*)(rowp + bj * HALF) = w; } }
; template <class Epi, class Sched, bool ALIGN_EPI = false, bool SP2 = false>
; __device__ __forceinline__ void gemm_phase(PG8_LAS unsigned char* lds, const Gemm g, const Sched& S, const Epi& E, int wave0) {
;     ...
;         if constexpr (!Epi::AFTER_DRAIN) { E(acc, cur, wr, wc, fr, fq); S.done(cur); }
;         if (!has_next) break;
; #pragma unroll
;         for (int a = 0; a < 2; ++a)
; #pragma unroll
;             for (int b = 0; b < 2; ++b)
; #pragma unroll
;                 for (int m = 0; m < 4; ++m)
; #pragma unroll
;                     for (int n = 0; n < 2; ++n) acc[a][b][m][n] = (f32x4){0.f, 0.f, 0.f, 0.f};
;         cur = nxt; cA = nA; cB = nB; ++ui;
;         if constexpr (ALIGN_EPI) { if (wr == 1) PG8_BAR; }
.LBB0_127:
	v_readlane_b32 s2, v240, 12
	v_readlane_b32 s3, v240, 13
	v_mov_b32_e32 v17, v16
	v_cvt_pk_bf16_f32 v12, v12, v13
	v_cvt_pk_bf16_f32 v13, v14, v15
	v_cvt_pk_bf16_f32 v14, v18, v19
	v_cvt_pk_bf16_f32 v15, v10, v11
	s_nop 0
	v_mov_b64_e32 v[8:9], s[2:3]
	v_mad_i64_i32 v[8:9], s[2:3], v144, s91, v[8:9]
	v_mov_b32_e32 v10, v16
	v_mov_b32_e32 v11, v16
	v_lshl_add_u64 v[8:9], v[120:121], 1, v[8:9]
	v_pk_mul_f32 v[6:7], v[6:7], v[10:11]
	v_pk_mul_f32 v[4:5], v[4:5], v[16:17]
	v_pk_mul_f32 v[2:3], v[2:3], v[10:11]
	s_and_b64 vcc, exec, s[6:7]
	v_pk_mul_f32 v[0:1], v[0:1], v[16:17]
	global_store_dwordx4 v[8:9], v[12:15], off sc1
	s_cbranch_vccnz .LBB0_129
	v_pk_mul_f32 v[10:11], v[4:5], s[16:17] op_sel_hi:[1,0]
	v_mov_b64_e32 v[14:15], s[20:21]
	v_med3_f32 v10, v10, s90, v173
	v_med3_f32 v11, v11, s90, v173
	v_pk_mul_f32 v[12:13], v[10:11], v[10:11]
	v_pk_mul_f32 v[4:5], v[4:5], 0.5 op_sel_hi:[1,0]
	v_pk_fma_f32 v[16:17], v[12:13], s[18:19], v[14:15] op_sel_hi:[1,0,0] neg_lo:[1,0,0] neg_hi:[1,0,0]
	s_nop 0
	v_pk_fma_f32 v[16:17], v[12:13], v[16:17], s[28:29] op_sel_hi:[1,1,0]
	s_nop 0
	v_pk_fma_f32 v[16:17], v[12:13], v[16:17], s[30:31] op_sel_hi:[1,1,0]
	s_nop 0
	v_pk_fma_f32 v[16:17], v[12:13], v[16:17], s[34:35] op_sel_hi:[1,1,0]
	s_nop 0
	v_pk_fma_f32 v[16:17], v[12:13], v[16:17], s[36:37] op_sel_hi:[1,1,0]
	s_nop 0
	v_pk_fma_f32 v[16:17], v[12:13], v[16:17], s[38:39] op_sel_hi:[1,1,0]
	s_nop 0
	v_pk_fma_f32 v[12:13], v[12:13], v[16:17], s[40:41] op_sel_hi:[1,1,0]
	s_nop 0
	v_pk_mul_f32 v[10:11], v[10:11], v[12:13]
	s_nop 0
	v_pk_fma_f32 v[4:5], v[4:5], v[10:11], v[4:5]
	v_pk_mul_f32 v[10:11], v[6:7], s[16:17] op_sel_hi:[1,0]
	v_pk_mul_f32 v[6:7], v[6:7], 0.5 op_sel_hi:[1,0]
	v_med3_f32 v10, v10, s90, v173
	v_med3_f32 v11, v11, s90, v173
	v_pk_mul_f32 v[12:13], v[10:11], v[10:11]
	s_nop 0
	v_pk_fma_f32 v[16:17], v[12:13], s[18:19], v[14:15] op_sel_hi:[1,0,0] neg_lo:[1,0,0] neg_hi:[1,0,0]
	s_nop 0
	v_pk_fma_f32 v[16:17], v[12:13], v[16:17], s[28:29] op_sel_hi:[1,1,0]
	s_nop 0
	v_pk_fma_f32 v[16:17], v[12:13], v[16:17], s[30:31] op_sel_hi:[1,1,0]
	s_nop 0
	v_pk_fma_f32 v[16:17], v[12:13], v[16:17], s[34:35] op_sel_hi:[1,1,0]
	s_nop 0
	v_pk_fma_f32 v[16:17], v[12:13], v[16:17], s[36:37] op_sel_hi:[1,1,0]
	s_nop 0
	v_pk_fma_f32 v[16:17], v[12:13], v[16:17], s[38:39] op_sel_hi:[1,1,0]
	s_nop 0
	v_pk_fma_f32 v[12:13], v[12:13], v[16:17], s[40:41] op_sel_hi:[1,1,0]
	s_nop 0
	v_pk_mul_f32 v[10:11], v[10:11], v[12:13]
	s_nop 0
	v_pk_fma_f32 v[6:7], v[6:7], v[10:11], v[6:7]
	v_pk_mul_f32 v[10:11], v[0:1], s[16:17] op_sel_hi:[1,0]
	v_pk_mul_f32 v[0:1], v[0:1], 0.5 op_sel_hi:[1,0]
	v_med3_f32 v10, v10, s90, v173
	v_med3_f32 v11, v11, s90, v173
	v_pk_mul_f32 v[12:13], v[10:11], v[10:11]
	s_nop 0
	v_pk_fma_f32 v[16:17], v[12:13], s[18:19], v[14:15] op_sel_hi:[1,0,0] neg_lo:[1,0,0] neg_hi:[1,0,0]
	s_nop 0
	v_pk_fma_f32 v[16:17], v[12:13], v[16:17], s[28:29] op_sel_hi:[1,1,0]
	s_nop 0
	v_pk_fma_f32 v[16:17], v[12:13], v[16:17], s[30:31] op_sel_hi:[1,1,0]
	s_nop 0
	v_pk_fma_f32 v[16:17], v[12:13], v[16:17], s[34:35] op_sel_hi:[1,1,0]
	s_nop 0
	v_pk_fma_f32 v[16:17], v[12:13], v[16:17], s[36:37] op_sel_hi:[1,1,0]
	s_nop 0
	v_pk_fma_f32 v[16:17], v[12:13], v[16:17], s[38:39] op_sel_hi:[1,1,0]
	s_nop 0
	v_pk_fma_f32 v[12:13], v[12:13], v[16:17], s[40:41] op_sel_hi:[1,1,0]
	s_nop 0
	v_pk_mul_f32 v[10:11], v[10:11], v[12:13]
	s_nop 0
	v_pk_fma_f32 v[0:1], v[0:1], v[10:11], v[0:1]
	v_pk_mul_f32 v[10:11], v[2:3], s[16:17] op_sel_hi:[1,0]
	v_pk_mul_f32 v[2:3], v[2:3], 0.5 op_sel_hi:[1,0]
	v_med3_f32 v10, v10, s90, v173
	v_med3_f32 v11, v11, s90, v173
	v_pk_mul_f32 v[12:13], v[10:11], v[10:11]
	s_nop 0
	v_pk_fma_f32 v[14:15], v[12:13], s[18:19], v[14:15] op_sel_hi:[1,0,0] neg_lo:[1,0,0] neg_hi:[1,0,0]
	s_nop 0
	v_pk_fma_f32 v[14:15], v[12:13], v[14:15], s[28:29] op_sel_hi:[1,1,0]
	s_nop 0
	v_pk_fma_f32 v[14:15], v[12:13], v[14:15], s[30:31] op_sel_hi:[1,1,0]
	s_nop 0
	v_pk_fma_f32 v[14:15], v[12:13], v[14:15], s[34:35] op_sel_hi:[1,1,0]
	s_nop 0
	v_pk_fma_f32 v[14:15], v[12:13], v[14:15], s[36:37] op_sel_hi:[1,1,0]
	s_nop 0
	v_pk_fma_f32 v[14:15], v[12:13], v[14:15], s[38:39] op_sel_hi:[1,1,0]
	s_nop 0
	v_pk_fma_f32 v[12:13], v[12:13], v[14:15], s[40:41] op_sel_hi:[1,1,0]
	s_nop 0
	v_pk_mul_f32 v[10:11], v[10:11], v[12:13]
	s_nop 0
	v_pk_fma_f32 v[2:3], v[2:3], v[10:11], v[2:3]
.LBB0_129:
	s_andn2_b64 vcc, exec, s[4:5]
	s_mov_b64 s[2:3], -1
	v_cvt_pk_bf16_f32 v4, v4, v5
	v_cvt_pk_bf16_f32 v5, v6, v7
	v_cvt_pk_bf16_f32 v6, v0, v1
	v_cvt_pk_bf16_f32 v7, v2, v3
	global_store_dwordx4 v[8:9], v[4:7], off offset:256 sc1
	s_cbranch_vccnz .LBB0_90
	s_andn2_b64 vcc, exec, s[58:59]
	s_cbranch_vccnz .LBB0_89
	s_barrier
	s_branch .LBB0_89

; __device__ __forceinline__ unsigned cvt_pk_bf16(float lo, float hi) { unsigned r; asm volatile("v_cvt_pk_bf16_f32 %0, %1, %2" : "=v"(r) : "v"(lo), "v"(hi)); return r; }
;     __device__ __forceinline__ void row_out(const f32x4 v0, const f32x4 v1, int row, int col, float& ss) const {
;         if (C) { float* rowp = C + (size_t)row * ldc + col; __builtin_nontemporal_store(v0, (f32x4*)rowp); __builtin_nontemporal_store(v1, (f32x4*)(rowp + 4)); }
;         if (wxb) { u32x4 w; w.x = cvt_pk_bf16(v0[0], v0[1]); w.y = cvt_pk_bf16(v0[2], v0[3]); w.z = cvt_pk_bf16(v1[0], v1[1]); w.w = cvt_pk_bf16(v1[2], v1[3]);
;             *(u32x4*)(XB0 + (size_t)row * ldc + col) = w;
;             ss += (v0[0] * v0[0] + v0[1] * v0[1]) + (v0[2] * v0[2] + v0[3] * v0[3]) + (v1[0] * v1[0] + v1[1] * v1[1]) + (v1[2] * v1[2] + v1[3] * v1[3]); }
;     __device__ __forceinline__ void operator()(const f32x4 (&acc)[2][2][4][2], const Unit& u, int wr, int wc, int fr, int fq) const {
;     ...
;               for (int mh = 0; mh < 4; mh += 2) {
;                 u32x4 rw[2][2];
; #pragma unroll
;                 for (int mm = 0; mm < 2; ++mm) { const int row = row0 + ai * HALF + (mh + mm) * 16;
; #pragma unroll
;                     for (int bj = 0; bj < 2; ++bj) if (bj == 0 || !u.q) rw[mm][bj] = *(const u32x4*)(XB0 + (size_t)row * ldc + col0 + bj * HALF); }
; #pragma unroll
;                 for (int mm = 0; mm < 2; ++mm) { const int m = mh + mm, row = row0 + ai * HALF + m * 16; float ss = 0.f;
; #pragma unroll
;                     for (int bj = 0; bj < 2; ++bj) if (bj == 0 || !u.q) { const u32x4 w = rw[mm][bj];
;                         const f32x4 v0 = acc[ai][bj][m][0] + (f32x4){bf_lo(w.x), bf_hi(w.x), bf_lo(w.y), bf_hi(w.y)}, v1 = acc[ai][bj][m][1] + (f32x4){bf_lo(w.z), bf_hi(w.z), bf_lo(w.w), bf_hi(w.w)};
;                         row_out(v0, v1, row, col0 + bj * HALF, ss); }
;                     if (wxb) { ss += __shfl_xor(ss, 16); ss += __shfl_xor(ss, 32); if (fq == 0) unsafeAtomicAdd(SS + row, ss); } }
.LBB0_366:
	v_mov_b32_e32 v128, v163
	v_mov_b32_e32 v169, v162
	s_add_i32 s0, s0, s39
	v_and_b32_e32 v183, 64, v168
	v_add_u32_e32 v154, s0, v128
	s_add_i32 s0, s49, s40
	v_lshl_add_u32 v152, v169, 3, s0
	v_ashrrev_i32_e32 v153, 31, v152
	v_lshlrev_b64 v[178:179], 1, v[152:153]
	v_ashrrev_i32_e32 v155, 31, v154
	v_lshl_add_u64 v[156:157], s[96:97], 0, v[178:179]
	v_lshlrev_b64 v[180:181], 11, v[154:155]
	v_lshl_add_u64 v[128:129], v[156:157], 0, v[180:181]
	global_load_dwordx4 v[170:173], v[128:129], off
	global_load_dwordx4 v[174:177], v[128:129], off offset:256
	v_add_u32_e32 v158, 16, v154
	v_ashrrev_i32_e32 v159, 31, v158
	v_lshlrev_b64 v[160:161], 11, v[158:159]
	v_lshl_add_u64 v[128:129], v[156:157], 0, v[160:161]
	global_load_dwordx4 v[132:135], v[128:129], off
	s_nop 0
	global_load_dwordx4 v[128:131], v[128:129], off offset:256
	v_xor_b32_e32 v182, 16, v168
	v_add_u32_e32 v183, 64, v183
	v_xor_b32_e32 v184, 32, v168
	v_cmp_lt_i32_e64 s[0:1], v182, v183
	v_cmp_eq_u32_e32 vcc, 0, v169
	v_lshl_add_u64 v[180:181], s[96:97], 0, v[180:181]
	v_cndmask_b32_e64 v169, v168, v182, s[0:1]
	v_cmp_lt_i32_e64 s[0:1], v184, v183
	v_lshl_add_u64 v[178:179], v[180:181], 0, v[178:179]
	v_lshlrev_b32_e32 v169, 2, v169
	v_cndmask_b32_e64 v188, v168, v184, s[0:1]
	s_waitcnt vmcnt(0)
	v_lshlrev_b32_e32 v180, 16, v170
	v_and_b32_e32 v181, 0xffff0000, v170
	v_lshlrev_b32_e32 v170, 16, v171
	v_and_b32_e32 v171, 0xffff0000, v171
	v_lshlrev_b32_e32 v184, 16, v174
	v_and_b32_e32 v185, 0xffff0000, v174
	v_lshlrev_b32_e32 v174, 16, v175
	v_and_b32_e32 v175, 0xffff0000, v175
	v_lshlrev_b32_e32 v182, 16, v172
	v_and_b32_e32 v183, 0xffff0000, v172
	v_lshlrev_b32_e32 v172, 16, v173
	v_and_b32_e32 v173, 0xffff0000, v173
	v_lshlrev_b32_e32 v186, 16, v176
	v_and_b32_e32 v187, 0xffff0000, v176
	v_lshlrev_b32_e32 v176, 16, v177
	v_and_b32_e32 v177, 0xffff0000, v177
	v_pk_add_f32 v[126:127], v[126:127], v[170:171]
	v_pk_add_f32 v[124:125], v[124:125], v[180:181]
	v_pk_add_f32 v[118:119], v[118:119], v[174:175]
	v_pk_add_f32 v[116:117], v[116:117], v[184:185]
	v_pk_add_f32 v[122:123], v[122:123], v[172:173]
	v_pk_add_f32 v[120:121], v[120:121], v[182:183]
	v_pk_add_f32 v[170:171], v[114:115], v[176:177]
	v_pk_add_f32 v[172:173], v[112:113], v[186:187]
	v_mul_f32_e32 v114, v125, v125
	v_mul_f32_e32 v115, v127, v127
	v_mul_f32_e32 v176, v117, v117
	v_mul_f32_e32 v177, v119, v119
	v_cvt_pk_bf16_f32 v112, v124, v125
	v_mul_f32_e32 v125, v121, v121
	v_mul_f32_e32 v175, v173, v173
	v_fmac_f32_e32 v114, v124, v124
	v_fmac_f32_e32 v115, v126, v126
	v_fmac_f32_e32 v176, v116, v116
	v_fmac_f32_e32 v177, v118, v118
	v_cvt_pk_bf16_f32 v113, v126, v127
	v_mul_f32_e32 v127, v123, v123
	v_mul_f32_e32 v174, v171, v171
	v_fmac_f32_e32 v125, v120, v120
	v_fmac_f32_e32 v175, v172, v172
	v_add_f32_e32 v114, v114, v115
	v_add_f32_e32 v115, v176, v177
	v_fmac_f32_e32 v127, v122, v122
	v_fmac_f32_e32 v174, v170, v170
	v_add_f32_e32 v114, v125, v114
	v_add_f32_e32 v115, v175, v115
	v_add_f32_e32 v114, v127, v114
	v_add_f32_e32 v115, v174, v115
	v_add_f32_e32 v124, v114, v115
	ds_bpermute_b32 v125, v169, v124
	v_cvt_pk_bf16_f32 v114, v120, v121
	v_cvt_pk_bf16_f32 v115, v122, v123
	global_store_dwordx4 v[178:179], v[112:115], off sc1
	v_cvt_pk_bf16_f32 v116, v116, v117
	v_cvt_pk_bf16_f32 v117, v118, v119
	v_cvt_pk_bf16_f32 v118, v172, v173
	v_cvt_pk_bf16_f32 v119, v170, v171
	global_store_dwordx4 v[178:179], v[116:119], off offset:256 sc1
	s_waitcnt lgkmcnt(0)
	v_add_f32_e32 v113, v124, v125
	v_lshlrev_b32_e32 v112, 2, v188
	ds_bpermute_b32 v114, v112, v113
	s_and_saveexec_b64 s[0:1], vcc
	s_cbranch_execz .LBB0_368
	s_waitcnt lgkmcnt(0)
	v_add_f32_e32 v113, v113, v114
	v_lshl_add_u64 v[114:115], v[154:155], 2, s[12:13]
	global_atomic_add_f32 v[114:115], v113, off
.LBB0_368:
	s_or_b64 exec, exec, s[0:1]
	s_waitcnt lgkmcnt(0)
	v_lshlrev_b32_e32 v114, 16, v132
	v_and_b32_e32 v115, 0xffff0000, v132
	v_lshlrev_b32_e32 v116, 16, v133
	v_and_b32_e32 v117, 0xffff0000, v133
	v_pk_add_f32 v[108:109], v[108:109], v[114:115]
	v_lshlrev_b32_e32 v114, 16, v134
	v_and_b32_e32 v115, 0xffff0000, v134
	v_pk_add_f32 v[110:111], v[110:111], v[116:117]
	v_pk_add_f32 v[114:115], v[104:105], v[114:115]
	v_cvt_pk_bf16_f32 v104, v108, v109
	v_mul_f32_e32 v109, v109, v109
	v_fmac_f32_e32 v109, v108, v108
	v_mul_f32_e32 v108, v111, v111
	v_fmac_f32_e32 v108, v110, v110
	v_lshlrev_b32_e32 v116, 16, v135
	v_and_b32_e32 v117, 0xffff0000, v135
	v_add_f32_e32 v108, v109, v108
	v_mul_f32_e32 v109, v115, v115
	v_pk_add_f32 v[116:117], v[106:107], v[116:117]
	v_fmac_f32_e32 v109, v114, v114
	v_add_f32_e32 v108, v109, v108
	v_mul_f32_e32 v109, v117, v117
	v_fmac_f32_e32 v109, v116, v116
	v_cvt_pk_bf16_f32 v105, v110, v111
	v_add_f32_e32 v113, v109, v108
	v_lshlrev_b32_e32 v108, 16, v128
	v_and_b32_e32 v109, 0xffff0000, v128
	v_lshlrev_b32_e32 v110, 16, v129
	v_and_b32_e32 v111, 0xffff0000, v129
	v_pk_add_f32 v[102:103], v[102:103], v[110:111]
	v_pk_add_f32 v[100:101], v[100:101], v[108:109]
	v_lshlrev_b32_e32 v108, 16, v130
	v_and_b32_e32 v109, 0xffff0000, v130
	v_lshlrev_b32_e32 v110, 16, v131
	v_and_b32_e32 v111, 0xffff0000, v131
	v_pk_add_f32 v[110:111], v[98:99], v[110:111]
	v_pk_add_f32 v[108:109], v[96:97], v[108:109]
	v_mul_f32_e32 v98, v101, v101
	v_mul_f32_e32 v99, v103, v103
	v_mul_f32_e32 v97, v109, v109
	v_fmac_f32_e32 v98, v100, v100
	v_fmac_f32_e32 v99, v102, v102
	v_mul_f32_e32 v96, v111, v111
	v_fmac_f32_e32 v97, v108, v108
	v_add_f32_e32 v98, v98, v99
	v_fmac_f32_e32 v96, v110, v110
	v_add_f32_e32 v97, v97, v98
	v_add_f32_e32 v96, v96, v97
	v_add_f32_e32 v99, v113, v96
	ds_bpermute_b32 v113, v169, v99
	v_lshl_add_u64 v[96:97], s[96:97], 0, v[160:161]
	v_cvt_pk_bf16_f32 v106, v114, v115
	v_lshl_add_u64 v[114:115], v[152:153], 1, v[96:97]
	v_cvt_pk_bf16_f32 v107, v116, v117
	s_waitcnt lgkmcnt(0)
	v_add_f32_e32 v96, v99, v113
	ds_bpermute_b32 v97, v112, v96
	global_store_dwordx4 v[114:115], v[104:107], off sc1
	v_cvt_pk_bf16_f32 v98, v100, v101
	v_cvt_pk_bf16_f32 v99, v102, v103
	v_cvt_pk_bf16_f32 v100, v108, v109
	v_cvt_pk_bf16_f32 v101, v110, v111
	global_store_dwordx4 v[114:115], v[98:101], off offset:256 sc1
	s_and_saveexec_b64 s[0:1], vcc
	s_cbranch_execz .LBB0_370
	s_waitcnt lgkmcnt(0)
	v_add_f32_e32 v98, v96, v97
	v_lshl_add_u64 v[96:97], v[158:159], 2, s[12:13]
	global_atomic_add_f32 v[96:97], v98, off
; __device__ __forceinline__ unsigned cvt_pk_bf16(float lo, float hi) { unsigned r; asm volatile("v_cvt_pk_bf16_f32 %0, %1, %2" : "=v"(r) : "v"(lo), "v"(hi)); return r; }
;     __device__ __forceinline__ void row_out(const f32x4 v0, const f32x4 v1, int row, int col, float& ss) const {
;         if (C) { float* rowp = C + (size_t)row * ldc + col; __builtin_nontemporal_store(v0, (f32x4*)rowp); __builtin_nontemporal_store(v1, (f32x4*)(rowp + 4)); }
;         if (wxb) { u32x4 w; w.x = cvt_pk_bf16(v0[0], v0[1]); w.y = cvt_pk_bf16(v0[2], v0[3]); w.z = cvt_pk_bf16(v1[0], v1[1]); w.w = cvt_pk_bf16(v1[2], v1[3]);
;             *(u32x4*)(XB0 + (size_t)row * ldc + col) = w;
;             ss += (v0[0] * v0[0] + v0[1] * v0[1]) + (v0[2] * v0[2] + v0[3] * v0[3]) + (v1[0] * v1[0] + v1[1] * v1[1]) + (v1[2] * v1[2] + v1[3] * v1[3]); }
;     __device__ __forceinline__ void operator()(const f32x4 (&acc)[2][2][4][2], const Unit& u, int wr, int wc, int fr, int fq) const {
;     ...
;               for (int mh = 0; mh < 4; mh += 2) {
;                 u32x4 rw[2][2];
; #pragma unroll
;                 for (int mm = 0; mm < 2; ++mm) { const int row = row0 + ai * HALF + (mh + mm) * 16;
; #pragma unroll
;                     for (int bj = 0; bj < 2; ++bj) if (bj == 0 || !u.q) rw[mm][bj] = *(const u32x4*)(XB0 + (size_t)row * ldc + col0 + bj * HALF); }
; #pragma unroll
;                 for (int mm = 0; mm < 2; ++mm) { const int m = mh + mm, row = row0 + ai * HALF + m * 16; float ss = 0.f;
; #pragma unroll
;                     for (int bj = 0; bj < 2; ++bj) if (bj == 0 || !u.q) { const u32x4 w = rw[mm][bj];
;                         const f32x4 v0 = acc[ai][bj][m][0] + (f32x4){bf_lo(w.x), bf_hi(w.x), bf_lo(w.y), bf_hi(w.y)}, v1 = acc[ai][bj][m][1] + (f32x4){bf_lo(w.z), bf_hi(w.z), bf_lo(w.w), bf_hi(w.w)};
;                         row_out(v0, v1, row, col0 + bj * HALF, ss); }
;                     if (wxb) { ss += __shfl_xor(ss, 16); ss += __shfl_xor(ss, 32); if (fq == 0) unsafeAtomicAdd(SS + row, ss); } }
.LBB0_370:
	s_or_b64 exec, exec, s[0:1]
	v_add_u32_e32 v108, 32, v154
	v_ashrrev_i32_e32 v109, 31, v108
	v_lshlrev_b64 v[110:111], 11, v[108:109]
	s_waitcnt lgkmcnt(0)
	v_lshl_add_u64 v[96:97], v[156:157], 0, v[110:111]
	global_load_dwordx4 v[114:117], v[96:97], off
	global_load_dwordx4 v[118:121], v[96:97], off offset:256
	v_add_u32_e32 v104, 48, v154
	v_ashrrev_i32_e32 v105, 31, v104
	v_lshlrev_b64 v[106:107], 11, v[104:105]
	v_lshl_add_u64 v[96:97], v[156:157], 0, v[106:107]
	global_load_dwordx4 v[100:103], v[96:97], off
	s_nop 0
	global_load_dwordx4 v[96:99], v[96:97], off offset:256
	s_waitcnt vmcnt(3)
	v_lshlrev_b32_e32 v122, 16, v114
	v_and_b32_e32 v123, 0xffff0000, v114
	v_lshlrev_b32_e32 v114, 16, v115
	v_and_b32_e32 v115, 0xffff0000, v115
	s_waitcnt vmcnt(2)
	v_lshlrev_b32_e32 v126, 16, v118
	v_and_b32_e32 v127, 0xffff0000, v118
	v_lshlrev_b32_e32 v118, 16, v119
	v_and_b32_e32 v119, 0xffff0000, v119
	v_lshlrev_b32_e32 v124, 16, v116
	v_and_b32_e32 v125, 0xffff0000, v116
	v_lshlrev_b32_e32 v116, 16, v117
	v_and_b32_e32 v117, 0xffff0000, v117
	v_lshlrev_b32_e32 v128, 16, v120
	v_and_b32_e32 v129, 0xffff0000, v120
	v_lshlrev_b32_e32 v120, 16, v121
	v_and_b32_e32 v121, 0xffff0000, v121
	v_pk_add_f32 v[94:95], v[94:95], v[114:115]
	v_pk_add_f32 v[92:93], v[92:93], v[122:123]
	v_pk_add_f32 v[86:87], v[86:87], v[118:119]
	v_pk_add_f32 v[84:85], v[84:85], v[126:127]
	v_pk_add_f32 v[90:91], v[90:91], v[116:117]
	v_pk_add_f32 v[88:89], v[88:89], v[124:125]
	v_pk_add_f32 v[114:115], v[82:83], v[120:121]
	v_pk_add_f32 v[116:117], v[80:81], v[128:129]
	v_cvt_pk_bf16_f32 v80, v92, v93
	v_cvt_pk_bf16_f32 v81, v94, v95
	v_mul_f32_e32 v93, v93, v93
	v_mul_f32_e32 v95, v95, v95
	v_mul_f32_e32 v119, v85, v85
	v_mul_f32_e32 v120, v87, v87
	v_cvt_pk_bf16_f32 v82, v88, v89
	v_cvt_pk_bf16_f32 v83, v90, v91
	v_mul_f32_e32 v89, v89, v89
	v_mul_f32_e32 v91, v91, v91
	v_mul_f32_e32 v118, v117, v117
	v_fmac_f32_e32 v93, v92, v92
	v_fmac_f32_e32 v95, v94, v94
	v_fmac_f32_e32 v119, v84, v84
	v_fmac_f32_e32 v120, v86, v86
	v_mul_f32_e32 v113, v115, v115
	v_fmac_f32_e32 v89, v88, v88
	v_fmac_f32_e32 v91, v90, v90
	v_fmac_f32_e32 v118, v116, v116
	v_add_f32_e32 v88, v93, v95
	v_add_f32_e32 v90, v119, v120
	v_fmac_f32_e32 v113, v114, v114
	v_add_f32_e32 v88, v89, v88
	v_add_f32_e32 v89, v118, v90
	v_add_f32_e32 v88, v91, v88
	v_add_f32_e32 v89, v113, v89
	v_add_f32_e32 v90, v88, v89
	ds_bpermute_b32 v91, v169, v90
	v_lshl_add_u64 v[88:89], s[96:97], 0, v[110:111]
	v_lshl_add_u64 v[88:89], v[152:153], 1, v[88:89]
	global_store_dwordx4 v[88:89], v[80:83], off sc1
	s_waitcnt lgkmcnt(0)
	s_nop 0
	v_add_f32_e32 v80, v90, v91
	ds_bpermute_b32 v81, v112, v80
	v_cvt_pk_bf16_f32 v82, v84, v85
	v_cvt_pk_bf16_f32 v83, v86, v87
	v_cvt_pk_bf16_f32 v84, v116, v117
	v_cvt_pk_bf16_f32 v85, v114, v115
	global_store_dwordx4 v[88:89], v[82:85], off offset:256 sc1
	s_and_saveexec_b64 s[0:1], vcc
	s_cbranch_execz .LBB0_372
	s_waitcnt lgkmcnt(0)
	v_add_f32_e32 v82, v80, v81
	v_lshl_add_u64 v[80:81], v[108:109], 2, s[12:13]
	global_atomic_add_f32 v[80:81], v82, off
.LBB0_372:
	s_or_b64 exec, exec, s[0:1]
	s_waitcnt vmcnt(3)
	v_lshlrev_b32_e32 v80, 16, v100
	s_waitcnt lgkmcnt(0)
	v_and_b32_e32 v81, 0xffff0000, v100
	v_lshlrev_b32_e32 v82, 16, v101
	v_and_b32_e32 v83, 0xffff0000, v101
	v_pk_add_f32 v[76:77], v[76:77], v[80:81]
	v_lshlrev_b32_e32 v80, 16, v102
	v_and_b32_e32 v81, 0xffff0000, v102
	v_pk_add_f32 v[78:79], v[78:79], v[82:83]
	v_pk_add_f32 v[80:81], v[72:73], v[80:81]
	v_cvt_pk_bf16_f32 v72, v76, v77
	v_mul_f32_e32 v77, v77, v77
	v_fmac_f32_e32 v77, v76, v76
	v_mul_f32_e32 v76, v79, v79
	v_fmac_f32_e32 v76, v78, v78
	v_lshlrev_b32_e32 v82, 16, v103
	v_and_b32_e32 v83, 0xffff0000, v103
	v_add_f32_e32 v76, v77, v76
	v_mul_f32_e32 v77, v81, v81
	v_pk_add_f32 v[82:83], v[74:75], v[82:83]
	v_fmac_f32_e32 v77, v80, v80
	v_add_f32_e32 v76, v77, v76
	v_mul_f32_e32 v77, v83, v83
	v_fmac_f32_e32 v77, v82, v82
	v_cvt_pk_bf16_f32 v73, v78, v79
	v_cvt_pk_bf16_f32 v74, v80, v81
	v_add_f32_e32 v80, v77, v76
	s_waitcnt vmcnt(2)
	v_lshlrev_b32_e32 v76, 16, v96
	v_and_b32_e32 v77, 0xffff0000, v96
	v_lshlrev_b32_e32 v78, 16, v97
	v_and_b32_e32 v79, 0xffff0000, v97
	v_pk_add_f32 v[70:71], v[70:71], v[78:79]
	v_pk_add_f32 v[68:69], v[68:69], v[76:77]
	v_lshlrev_b32_e32 v76, 16, v98
	v_and_b32_e32 v77, 0xffff0000, v98
	v_lshlrev_b32_e32 v78, 16, v99
	v_and_b32_e32 v79, 0xffff0000, v99
	v_pk_add_f32 v[78:79], v[66:67], v[78:79]
	v_pk_add_f32 v[76:77], v[64:65], v[76:77]
	v_mul_f32_e32 v66, v69, v69
	v_mul_f32_e32 v67, v71, v71
	v_mul_f32_e32 v65, v77, v77
	v_fmac_f32_e32 v66, v68, v68
	v_fmac_f32_e32 v67, v70, v70
	v_mul_f32_e32 v64, v79, v79
	v_fmac_f32_e32 v65, v76, v76
	v_add_f32_e32 v66, v66, v67
	v_fmac_f32_e32 v64, v78, v78
	v_add_f32_e32 v65, v65, v66
	v_add_f32_e32 v64, v64, v65
	v_add_f32_e32 v67, v80, v64
	v_cvt_pk_bf16_f32 v75, v82, v83
	ds_bpermute_b32 v82, v169, v67
	v_lshl_add_u64 v[64:65], s[96:97], 0, v[106:107]
	v_lshl_add_u64 v[80:81], v[152:153], 1, v[64:65]
	global_store_dwordx4 v[80:81], v[72:75], off sc1
	v_cvt_pk_bf16_f32 v66, v68, v69
	s_waitcnt lgkmcnt(0)
	v_add_f32_e32 v64, v67, v82
	ds_bpermute_b32 v65, v112, v64
	v_cvt_pk_bf16_f32 v67, v70, v71
	v_cvt_pk_bf16_f32 v68, v76, v77
	v_cvt_pk_bf16_f32 v69, v78, v79
	global_store_dwordx4 v[80:81], v[66:69], off offset:256 sc1
	s_and_saveexec_b64 s[0:1], vcc
	s_cbranch_execz .LBB0_374
	s_waitcnt lgkmcnt(0)
	v_add_f32_e32 v66, v64, v65
	v_lshl_add_u64 v[64:65], v[104:105], 2, s[12:13]
	global_atomic_add_f32 v[64:65], v66, off
; __device__ __forceinline__ unsigned cvt_pk_bf16(float lo, float hi) { unsigned r; asm volatile("v_cvt_pk_bf16_f32 %0, %1, %2" : "=v"(r) : "v"(lo), "v"(hi)); return r; }
;     __device__ __forceinline__ void row_out(const f32x4 v0, const f32x4 v1, int row, int col, float& ss) const {
;         if (C) { float* rowp = C + (size_t)row * ldc + col; __builtin_nontemporal_store(v0, (f32x4*)rowp); __builtin_nontemporal_store(v1, (f32x4*)(rowp + 4)); }
;         if (wxb) { u32x4 w; w.x = cvt_pk_bf16(v0[0], v0[1]); w.y = cvt_pk_bf16(v0[2], v0[3]); w.z = cvt_pk_bf16(v1[0], v1[1]); w.w = cvt_pk_bf16(v1[2], v1[3]);
;             *(u32x4*)(XB0 + (size_t)row * ldc + col) = w;
;             ss += (v0[0] * v0[0] + v0[1] * v0[1]) + (v0[2] * v0[2] + v0[3] * v0[3]) + (v1[0] * v1[0] + v1[1] * v1[1]) + (v1[2] * v1[2] + v1[3] * v1[3]); }
;     __device__ __forceinline__ void operator()(const f32x4 (&acc)[2][2][4][2], const Unit& u, int wr, int wc, int fr, int fq) const {
;     ...
;               for (int mh = 0; mh < 4; mh += 2) {
;                 u32x4 rw[2][2];
; #pragma unroll
;                 for (int mm = 0; mm < 2; ++mm) { const int row = row0 + ai * HALF + (mh + mm) * 16;
; #pragma unroll
;                     for (int bj = 0; bj < 2; ++bj) if (bj == 0 || !u.q) rw[mm][bj] = *(const u32x4*)(XB0 + (size_t)row * ldc + col0 + bj * HALF); }
; #pragma unroll
;                 for (int mm = 0; mm < 2; ++mm) { const int m = mh + mm, row = row0 + ai * HALF + m * 16; float ss = 0.f;
; #pragma unroll
;                     for (int bj = 0; bj < 2; ++bj) if (bj == 0 || !u.q) { const u32x4 w = rw[mm][bj];
;                         const f32x4 v0 = acc[ai][bj][m][0] + (f32x4){bf_lo(w.x), bf_hi(w.x), bf_lo(w.y), bf_hi(w.y)}, v1 = acc[ai][bj][m][1] + (f32x4){bf_lo(w.z), bf_hi(w.z), bf_lo(w.w), bf_hi(w.w)};
;                         row_out(v0, v1, row, col0 + bj * HALF, ss); }
;                     if (wxb) { ss += __shfl_xor(ss, 16); ss += __shfl_xor(ss, 32); if (fq == 0) unsafeAtomicAdd(SS + row, ss); } }
.LBB0_374:
	s_or_b64 exec, exec, s[0:1]
	v_add_u32_e32 v76, 0x80, v154
	v_ashrrev_i32_e32 v77, 31, v76
	v_lshlrev_b64 v[86:87], 11, v[76:77]
	s_waitcnt lgkmcnt(0)
	v_lshl_add_u64 v[64:65], v[156:157], 0, v[86:87]
	global_load_dwordx4 v[78:81], v[64:65], off
	global_load_dwordx4 v[82:85], v[64:65], off offset:256
	v_add_u32_e32 v72, 0x90, v154
	v_ashrrev_i32_e32 v73, 31, v72
	v_lshlrev_b64 v[74:75], 11, v[72:73]
	v_lshl_add_u64 v[64:65], v[156:157], 0, v[74:75]
	global_load_dwordx4 v[68:71], v[64:65], off
	s_nop 0
	global_load_dwordx4 v[64:67], v[64:65], off offset:256
	s_waitcnt vmcnt(3)
	v_lshlrev_b32_e32 v88, 16, v78
	v_and_b32_e32 v89, 0xffff0000, v78
	v_lshlrev_b32_e32 v78, 16, v79
	v_and_b32_e32 v79, 0xffff0000, v79
	s_waitcnt vmcnt(2)
	v_lshlrev_b32_e32 v92, 16, v82
	v_and_b32_e32 v93, 0xffff0000, v82
	v_lshlrev_b32_e32 v82, 16, v83
	v_and_b32_e32 v83, 0xffff0000, v83
	v_lshlrev_b32_e32 v90, 16, v80
	v_and_b32_e32 v91, 0xffff0000, v80
	v_lshlrev_b32_e32 v80, 16, v81
	v_and_b32_e32 v81, 0xffff0000, v81
	v_lshlrev_b32_e32 v94, 16, v84
	v_and_b32_e32 v95, 0xffff0000, v84
	v_lshlrev_b32_e32 v84, 16, v85
	v_and_b32_e32 v85, 0xffff0000, v85
	v_pk_add_f32 v[62:63], v[62:63], v[78:79]
	v_pk_add_f32 v[60:61], v[60:61], v[88:89]
	v_pk_add_f32 v[54:55], v[54:55], v[82:83]
	v_pk_add_f32 v[52:53], v[52:53], v[92:93]
	v_pk_add_f32 v[58:59], v[58:59], v[80:81]
	v_pk_add_f32 v[56:57], v[56:57], v[90:91]
	v_pk_add_f32 v[78:79], v[50:51], v[84:85]
	v_pk_add_f32 v[80:81], v[48:49], v[94:95]
	v_cvt_pk_bf16_f32 v48, v60, v61
	v_cvt_pk_bf16_f32 v49, v62, v63
	v_mul_f32_e32 v61, v61, v61
	v_mul_f32_e32 v63, v63, v63
	v_mul_f32_e32 v84, v53, v53
	v_mul_f32_e32 v85, v55, v55
	v_cvt_pk_bf16_f32 v50, v56, v57
	v_cvt_pk_bf16_f32 v51, v58, v59
	v_mul_f32_e32 v57, v57, v57
	v_mul_f32_e32 v59, v59, v59
	v_mul_f32_e32 v83, v81, v81
	v_fmac_f32_e32 v61, v60, v60
	v_fmac_f32_e32 v63, v62, v62
	v_fmac_f32_e32 v84, v52, v52
	v_fmac_f32_e32 v85, v54, v54
	v_mul_f32_e32 v82, v79, v79
	v_fmac_f32_e32 v57, v56, v56
	v_fmac_f32_e32 v59, v58, v58
	v_fmac_f32_e32 v83, v80, v80
	v_add_f32_e32 v56, v61, v63
	v_add_f32_e32 v58, v84, v85
	v_fmac_f32_e32 v82, v78, v78
	v_add_f32_e32 v56, v57, v56
	v_add_f32_e32 v57, v83, v58
	v_add_f32_e32 v56, v59, v56
	v_add_f32_e32 v57, v82, v57
	v_add_f32_e32 v58, v56, v57
	ds_bpermute_b32 v59, v169, v58
	v_lshl_add_u64 v[56:57], s[96:97], 0, v[86:87]
	v_lshl_add_u64 v[56:57], v[152:153], 1, v[56:57]
	global_store_dwordx4 v[56:57], v[48:51], off sc1
	s_waitcnt lgkmcnt(0)
	s_nop 0
	v_add_f32_e32 v48, v58, v59
	ds_bpermute_b32 v49, v112, v48
	v_cvt_pk_bf16_f32 v50, v52, v53
	v_cvt_pk_bf16_f32 v51, v54, v55
	v_cvt_pk_bf16_f32 v52, v80, v81
	v_cvt_pk_bf16_f32 v53, v78, v79
	global_store_dwordx4 v[56:57], v[50:53], off offset:256 sc1
	s_and_saveexec_b64 s[0:1], vcc
	s_cbranch_execz .LBB0_376
	s_waitcnt lgkmcnt(0)
	v_add_f32_e32 v50, v48, v49
	v_lshl_add_u64 v[48:49], v[76:77], 2, s[12:13]
	global_atomic_add_f32 v[48:49], v50, off
.LBB0_376:
	s_or_b64 exec, exec, s[0:1]
	s_waitcnt vmcnt(3)
	v_lshlrev_b32_e32 v48, 16, v68
	s_waitcnt lgkmcnt(0)
	v_and_b32_e32 v49, 0xffff0000, v68
	v_lshlrev_b32_e32 v50, 16, v69
	v_and_b32_e32 v51, 0xffff0000, v69
	v_pk_add_f32 v[44:45], v[44:45], v[48:49]
	v_lshlrev_b32_e32 v48, 16, v70
	v_and_b32_e32 v49, 0xffff0000, v70
	v_pk_add_f32 v[46:47], v[46:47], v[50:51]
	v_pk_add_f32 v[48:49], v[40:41], v[48:49]
	v_cvt_pk_bf16_f32 v40, v44, v45
	v_mul_f32_e32 v45, v45, v45
	v_fmac_f32_e32 v45, v44, v44
	v_mul_f32_e32 v44, v47, v47
	v_fmac_f32_e32 v44, v46, v46
	v_lshlrev_b32_e32 v50, 16, v71
	v_and_b32_e32 v51, 0xffff0000, v71
	v_add_f32_e32 v44, v45, v44
	v_mul_f32_e32 v45, v49, v49
	v_pk_add_f32 v[50:51], v[42:43], v[50:51]
	v_fmac_f32_e32 v45, v48, v48
	v_add_f32_e32 v44, v45, v44
	v_mul_f32_e32 v45, v51, v51
	v_fmac_f32_e32 v45, v50, v50
	v_cvt_pk_bf16_f32 v41, v46, v47
	v_cvt_pk_bf16_f32 v42, v48, v49
	v_add_f32_e32 v48, v45, v44
	s_waitcnt vmcnt(2)
	v_lshlrev_b32_e32 v44, 16, v64
	v_and_b32_e32 v45, 0xffff0000, v64
	v_lshlrev_b32_e32 v46, 16, v65
	v_and_b32_e32 v47, 0xffff0000, v65
	v_pk_add_f32 v[38:39], v[38:39], v[46:47]
	v_pk_add_f32 v[36:37], v[36:37], v[44:45]
	v_lshlrev_b32_e32 v44, 16, v66
	v_and_b32_e32 v45, 0xffff0000, v66
	v_lshlrev_b32_e32 v46, 16, v67
	v_and_b32_e32 v47, 0xffff0000, v67
	v_pk_add_f32 v[46:47], v[34:35], v[46:47]
	v_pk_add_f32 v[44:45], v[32:33], v[44:45]
	v_mul_f32_e32 v34, v37, v37
	v_mul_f32_e32 v35, v39, v39
	v_mul_f32_e32 v33, v45, v45
	v_fmac_f32_e32 v34, v36, v36
	v_fmac_f32_e32 v35, v38, v38
	v_mul_f32_e32 v32, v47, v47
	v_fmac_f32_e32 v33, v44, v44
	v_add_f32_e32 v34, v34, v35
	v_fmac_f32_e32 v32, v46, v46
	v_add_f32_e32 v33, v33, v34
	v_add_f32_e32 v32, v32, v33
	v_add_f32_e32 v35, v48, v32
	v_cvt_pk_bf16_f32 v43, v50, v51
	ds_bpermute_b32 v50, v169, v35
	v_lshl_add_u64 v[32:33], s[96:97], 0, v[74:75]
	v_lshl_add_u64 v[48:49], v[152:153], 1, v[32:33]
	global_store_dwordx4 v[48:49], v[40:43], off sc1
	v_cvt_pk_bf16_f32 v34, v36, v37
	s_waitcnt lgkmcnt(0)
	v_add_f32_e32 v32, v35, v50
	ds_bpermute_b32 v33, v112, v32
	v_cvt_pk_bf16_f32 v35, v38, v39
	v_cvt_pk_bf16_f32 v36, v44, v45
	v_cvt_pk_bf16_f32 v37, v46, v47
	global_store_dwordx4 v[48:49], v[34:37], off offset:256 sc1
	s_and_saveexec_b64 s[0:1], vcc
	s_cbranch_execz .LBB0_378
	s_waitcnt lgkmcnt(0)
	v_add_f32_e32 v34, v32, v33
	v_lshl_add_u64 v[32:33], v[72:73], 2, s[12:13]
	global_atomic_add_f32 v[32:33], v34, off
; __device__ __forceinline__ unsigned cvt_pk_bf16(float lo, float hi) { unsigned r; asm volatile("v_cvt_pk_bf16_f32 %0, %1, %2" : "=v"(r) : "v"(lo), "v"(hi)); return r; }
;     __device__ __forceinline__ void row_out(const f32x4 v0, const f32x4 v1, int row, int col, float& ss) const {
;         if (C) { float* rowp = C + (size_t)row * ldc + col; __builtin_nontemporal_store(v0, (f32x4*)rowp); __builtin_nontemporal_store(v1, (f32x4*)(rowp + 4)); }
;         if (wxb) { u32x4 w; w.x = cvt_pk_bf16(v0[0], v0[1]); w.y = cvt_pk_bf16(v0[2], v0[3]); w.z = cvt_pk_bf16(v1[0], v1[1]); w.w = cvt_pk_bf16(v1[2], v1[3]);
;             *(u32x4*)(XB0 + (size_t)row * ldc + col) = w;
;             ss += (v0[0] * v0[0] + v0[1] * v0[1]) + (v0[2] * v0[2] + v0[3] * v0[3]) + (v1[0] * v1[0] + v1[1] * v1[1]) + (v1[2] * v1[2] + v1[3] * v1[3]); }
;     __device__ __forceinline__ void operator()(const f32x4 (&acc)[2][2][4][2], const Unit& u, int wr, int wc, int fr, int fq) const {
;     ...
;               for (int mh = 0; mh < 4; mh += 2) {
;                 u32x4 rw[2][2];
; #pragma unroll
;                 for (int mm = 0; mm < 2; ++mm) { const int row = row0 + ai * HALF + (mh + mm) * 16;
; #pragma unroll
;                     for (int bj = 0; bj < 2; ++bj) if (bj == 0 || !u.q) rw[mm][bj] = *(const u32x4*)(XB0 + (size_t)row * ldc + col0 + bj * HALF); }
; #pragma unroll
;                 for (int mm = 0; mm < 2; ++mm) { const int m = mh + mm, row = row0 + ai * HALF + m * 16; float ss = 0.f;
; #pragma unroll
;                     for (int bj = 0; bj < 2; ++bj) if (bj == 0 || !u.q) { const u32x4 w = rw[mm][bj];
;                         const f32x4 v0 = acc[ai][bj][m][0] + (f32x4){bf_lo(w.x), bf_hi(w.x), bf_lo(w.y), bf_hi(w.y)}, v1 = acc[ai][bj][m][1] + (f32x4){bf_lo(w.z), bf_hi(w.z), bf_lo(w.w), bf_hi(w.w)};
;                         row_out(v0, v1, row, col0 + bj * HALF, ss); }
;                     if (wxb) { ss += __shfl_xor(ss, 16); ss += __shfl_xor(ss, 32); if (fq == 0) unsafeAtomicAdd(SS + row, ss); } }
.LBB0_378:
	s_or_b64 exec, exec, s[0:1]
	v_add_u32_e32 v44, 0xa0, v154
	v_ashrrev_i32_e32 v45, 31, v44
	v_lshlrev_b64 v[54:55], 11, v[44:45]
	s_waitcnt lgkmcnt(0)
	v_lshl_add_u64 v[32:33], v[156:157], 0, v[54:55]
	global_load_dwordx4 v[46:49], v[32:33], off
	global_load_dwordx4 v[50:53], v[32:33], off offset:256
	v_add_u32_e32 v40, 0xb0, v154
	v_ashrrev_i32_e32 v41, 31, v40
	v_lshlrev_b64 v[42:43], 11, v[40:41]
	v_lshl_add_u64 v[32:33], v[156:157], 0, v[42:43]
	global_load_dwordx4 v[36:39], v[32:33], off
	s_nop 0
	global_load_dwordx4 v[32:35], v[32:33], off offset:256
	s_waitcnt vmcnt(3)
	v_lshlrev_b32_e32 v56, 16, v46
	v_and_b32_e32 v57, 0xffff0000, v46
	v_lshlrev_b32_e32 v46, 16, v47
	v_and_b32_e32 v47, 0xffff0000, v47
	s_waitcnt vmcnt(2)
	v_lshlrev_b32_e32 v60, 16, v50
	v_and_b32_e32 v61, 0xffff0000, v50
	v_lshlrev_b32_e32 v50, 16, v51
	v_and_b32_e32 v51, 0xffff0000, v51
	v_lshlrev_b32_e32 v58, 16, v48
	v_and_b32_e32 v59, 0xffff0000, v48
	v_lshlrev_b32_e32 v48, 16, v49
	v_and_b32_e32 v49, 0xffff0000, v49
	v_lshlrev_b32_e32 v62, 16, v52
	v_and_b32_e32 v63, 0xffff0000, v52
	v_lshlrev_b32_e32 v52, 16, v53
	v_and_b32_e32 v53, 0xffff0000, v53
	v_pk_add_f32 v[30:31], v[30:31], v[46:47]
	v_pk_add_f32 v[28:29], v[28:29], v[56:57]
	v_pk_add_f32 v[22:23], v[22:23], v[50:51]
	v_pk_add_f32 v[20:21], v[20:21], v[60:61]
	v_pk_add_f32 v[26:27], v[26:27], v[48:49]
	v_pk_add_f32 v[24:25], v[24:25], v[58:59]
	v_pk_add_f32 v[46:47], v[18:19], v[52:53]
	v_pk_add_f32 v[48:49], v[16:17], v[62:63]
	v_cvt_pk_bf16_f32 v16, v28, v29
	v_cvt_pk_bf16_f32 v17, v30, v31
	v_mul_f32_e32 v29, v29, v29
	v_mul_f32_e32 v31, v31, v31
	v_mul_f32_e32 v52, v21, v21
	v_mul_f32_e32 v53, v23, v23
	v_cvt_pk_bf16_f32 v18, v24, v25
	v_cvt_pk_bf16_f32 v19, v26, v27
	v_mul_f32_e32 v25, v25, v25
	v_mul_f32_e32 v27, v27, v27
	v_mul_f32_e32 v51, v49, v49
	v_fmac_f32_e32 v29, v28, v28
	v_fmac_f32_e32 v31, v30, v30
	v_fmac_f32_e32 v52, v20, v20
	v_fmac_f32_e32 v53, v22, v22
	v_mul_f32_e32 v50, v47, v47
	v_fmac_f32_e32 v25, v24, v24
	v_fmac_f32_e32 v27, v26, v26
	v_fmac_f32_e32 v51, v48, v48
	v_add_f32_e32 v24, v29, v31
	v_add_f32_e32 v26, v52, v53
	v_fmac_f32_e32 v50, v46, v46
	v_add_f32_e32 v24, v25, v24
	v_add_f32_e32 v25, v51, v26
	v_add_f32_e32 v24, v27, v24
	v_add_f32_e32 v25, v50, v25
	v_add_f32_e32 v26, v24, v25
	ds_bpermute_b32 v27, v169, v26
	v_lshl_add_u64 v[24:25], s[96:97], 0, v[54:55]
	v_lshl_add_u64 v[24:25], v[152:153], 1, v[24:25]
	global_store_dwordx4 v[24:25], v[16:19], off sc1
	s_waitcnt lgkmcnt(0)
	s_nop 0
	v_add_f32_e32 v16, v26, v27
	ds_bpermute_b32 v17, v112, v16
	v_cvt_pk_bf16_f32 v18, v20, v21
	v_cvt_pk_bf16_f32 v19, v22, v23
	v_cvt_pk_bf16_f32 v20, v48, v49
	v_cvt_pk_bf16_f32 v21, v46, v47
	global_store_dwordx4 v[24:25], v[18:21], off offset:256 sc1
	s_and_saveexec_b64 s[0:1], vcc
	s_cbranch_execz .LBB0_380
	s_waitcnt lgkmcnt(0)
	v_add_f32_e32 v18, v16, v17
	v_lshl_add_u64 v[16:17], v[44:45], 2, s[12:13]
	global_atomic_add_f32 v[16:17], v18, off
.LBB0_380:
	s_or_b64 exec, exec, s[0:1]
	s_waitcnt vmcnt(3)
	v_lshlrev_b32_e32 v16, 16, v36
	s_waitcnt lgkmcnt(0)
	v_and_b32_e32 v17, 0xffff0000, v36
	v_lshlrev_b32_e32 v18, 16, v37
	v_and_b32_e32 v19, 0xffff0000, v37
	v_pk_add_f32 v[12:13], v[12:13], v[16:17]
	v_lshlrev_b32_e32 v16, 16, v38
	v_and_b32_e32 v17, 0xffff0000, v38
	v_pk_add_f32 v[14:15], v[14:15], v[18:19]
	v_pk_add_f32 v[16:17], v[8:9], v[16:17]
	v_cvt_pk_bf16_f32 v8, v12, v13
	v_mul_f32_e32 v13, v13, v13
	v_fmac_f32_e32 v13, v12, v12
	v_mul_f32_e32 v12, v15, v15
	v_fmac_f32_e32 v12, v14, v14
	v_lshlrev_b32_e32 v18, 16, v39
	v_and_b32_e32 v19, 0xffff0000, v39
	v_add_f32_e32 v12, v13, v12
	v_mul_f32_e32 v13, v17, v17
	v_pk_add_f32 v[18:19], v[10:11], v[18:19]
	v_fmac_f32_e32 v13, v16, v16
	v_add_f32_e32 v12, v13, v12
	v_mul_f32_e32 v13, v19, v19
	v_fmac_f32_e32 v13, v18, v18
	v_cvt_pk_bf16_f32 v9, v14, v15
	v_cvt_pk_bf16_f32 v10, v16, v17
	v_add_f32_e32 v16, v13, v12
	s_waitcnt vmcnt(2)
	v_lshlrev_b32_e32 v12, 16, v32
	v_and_b32_e32 v13, 0xffff0000, v32
	v_lshlrev_b32_e32 v14, 16, v33
	v_and_b32_e32 v15, 0xffff0000, v33
	v_pk_add_f32 v[6:7], v[6:7], v[14:15]
	v_pk_add_f32 v[4:5], v[4:5], v[12:13]
	v_lshlrev_b32_e32 v12, 16, v34
	v_and_b32_e32 v13, 0xffff0000, v34
	v_lshlrev_b32_e32 v14, 16, v35
	v_and_b32_e32 v15, 0xffff0000, v35
	v_pk_add_f32 v[14:15], v[2:3], v[14:15]
	v_pk_add_f32 v[12:13], v[0:1], v[12:13]
	v_mul_f32_e32 v2, v5, v5
	v_mul_f32_e32 v3, v7, v7
	v_mul_f32_e32 v1, v13, v13
	v_fmac_f32_e32 v2, v4, v4
	v_fmac_f32_e32 v3, v6, v6
	v_mul_f32_e32 v0, v15, v15
	v_fmac_f32_e32 v1, v12, v12
	v_add_f32_e32 v2, v2, v3
	v_fmac_f32_e32 v0, v14, v14
	v_add_f32_e32 v1, v1, v2
	v_add_f32_e32 v0, v0, v1
	v_add_f32_e32 v3, v16, v0
	v_cvt_pk_bf16_f32 v11, v18, v19
	ds_bpermute_b32 v18, v169, v3
	v_lshl_add_u64 v[0:1], s[96:97], 0, v[42:43]
	v_lshl_add_u64 v[16:17], v[152:153], 1, v[0:1]
	global_store_dwordx4 v[16:17], v[8:11], off sc1
	v_cvt_pk_bf16_f32 v2, v4, v5
	s_waitcnt lgkmcnt(0)
	v_add_f32_e32 v0, v3, v18
	ds_bpermute_b32 v1, v112, v0
	v_cvt_pk_bf16_f32 v3, v6, v7
	v_cvt_pk_bf16_f32 v4, v12, v13
	v_cvt_pk_bf16_f32 v5, v14, v15
	global_store_dwordx4 v[16:17], v[2:5], off offset:256 sc1
	s_and_saveexec_b64 s[0:1], vcc
	s_cbranch_execz .LBB0_382
	v_lshl_add_u64 v[2:3], v[40:41], 2, s[12:13]
	s_waitcnt lgkmcnt(0)
	v_add_f32_e32 v0, v0, v1
	global_atomic_add_f32 v[2:3], v0, off

; __device__ __forceinline__ unsigned cvt_pk_bf16(float lo, float hi) { unsigned r; asm volatile("v_cvt_pk_bf16_f32 %0, %1, %2" : "=v"(r) : "v"(lo), "v"(hi)); return r; }
; __device__ __forceinline__ f32x2 gelu_pk(f32x2 v) {
;     f32x2 x = v * 0.70710678118f;
;     x.x = __builtin_amdgcn_fmed3f(x.x, -2.9f, 2.9f); x.y = __builtin_amdgcn_fmed3f(x.y, -2.9f, 2.9f);
;     const f32x2 t = x * x;
;     f32x2 p = t * (-4.953124630e-07f) + 1.987094038e-05f;
;     p = p * t + (-3.472001117e-04f); p = p * t + 3.517547622e-03f; p = p * t + (-2.333305031e-02f); p = p * t + 1.087993085e-01f; p = p * t + (-3.740358949e-01f); p = p * t + 1.128076553e+00f;
;     const f32x2 hv = v * 0.5f;
;     return hv * (x * p) + hv;
; }
;     __device__ __forceinline__ void operator()(const f32x4 (&acc)[2][2][4][2], const Unit& u, int wr, int wc, int fr, int fq) const {
;     ...
;             for (int m = 0; m < 4; ++m) { bf16_t* rowp = O + (size_t)(row0 + ai * HALF + m * 16) * ldc + col0;
;                 const float rs = rsqrtf(rsv[ai][m] * (1.f / 1024.f) + 1e-6f);
; #pragma unroll
;                 for (int bj = 0; bj < 2; ++bj) if (bj == 0 || !u.q) { f32x4 v0 = acc[ai][bj][m][0] * rs, v1 = acc[ai][bj][m][1] * rs;
;                     if (act) { f32x2 a = gelu_pk((f32x2){v0[0], v0[1]}), b = gelu_pk((f32x2){v0[2], v0[3]}), c = gelu_pk((f32x2){v1[0], v1[1]}), d = gelu_pk((f32x2){v1[2], v1[3]});
;                         v0 = (f32x4){a.x, a.y, b.x, b.y}; v1 = (f32x4){c.x, c.y, d.x, d.y}; }
;                     u32x4 w; w.x = cvt_pk_bf16(v0[0], v0[1]); w.y = cvt_pk_bf16(v0[2], v0[3]); w.z = cvt_pk_bf16(v1[0], v1[1]); w.w = cvt_pk_bf16(v1[2], v1[3]);
;                     *(u32x4*)(rowp + bj * HALF) = w; } }
.LBB0_485:
	s_add_i32 s2, s84, s33
	v_lshl_add_u32 v120, v181, 3, s2
	v_lshlrev_b64 v[122:123], 10, v[158:159]
	v_ashrrev_i32_e32 v121, 31, v120
	v_lshl_add_u64 v[122:123], s[64:65], 0, v[122:123]
	v_lshl_add_u64 v[122:123], v[120:121], 1, v[122:123]
	v_cvt_pk_bf16_f32 v124, v124, v125
	v_cvt_pk_bf16_f32 v125, v126, v127
	v_cvt_pk_bf16_f32 v126, v164, v165
	v_cvt_pk_bf16_f32 v127, v162, v163
	global_store_dwordx4 v[122:123], v[124:127], off sc1
	v_mov_b32_e32 v161, v160
	v_pk_mul_f32 v[116:117], v[116:117], v[160:161]
	v_mov_b32_e32 v124, v160
	v_mov_b32_e32 v125, v160
	v_pk_mul_f32 v[118:119], v[118:119], v[124:125]
	v_pk_mul_f32 v[114:115], v[114:115], v[124:125]
	v_cndmask_b32_e64 v124, 0, 1, s[50:51]
	v_cmp_ne_u32_e64 s[10:11], 1, v124
	s_andn2_b64 vcc, exec, s[50:51]
	v_pk_mul_f32 v[112:113], v[112:113], v[160:161]
	s_cbranch_vccnz .LBB0_487
	v_pk_mul_f32 v[124:125], v[116:117], s[16:17] op_sel_hi:[1,0]
	v_mov_b64_e32 v[158:159], s[20:21]
	v_med3_f32 v124, v124, s70, v173
	v_med3_f32 v125, v125, s70, v173
	v_pk_mul_f32 v[126:127], v[124:125], v[124:125]
	v_pk_mul_f32 v[116:117], v[116:117], 0.5 op_sel_hi:[1,0]
	v_pk_fma_f32 v[160:161], v[126:127], s[18:19], v[158:159] op_sel_hi:[1,0,0] neg_lo:[1,0,0] neg_hi:[1,0,0]
	s_nop 0
	v_pk_fma_f32 v[160:161], v[126:127], v[160:161], s[28:29] op_sel_hi:[1,1,0]
	s_nop 0
	v_pk_fma_f32 v[160:161], v[126:127], v[160:161], s[30:31] op_sel_hi:[1,1,0]
	s_nop 0
	v_pk_fma_f32 v[160:161], v[126:127], v[160:161], s[34:35] op_sel_hi:[1,1,0]
	s_nop 0
	v_pk_fma_f32 v[160:161], v[126:127], v[160:161], s[36:37] op_sel_hi:[1,1,0]
	s_nop 0
	v_pk_fma_f32 v[160:161], v[126:127], v[160:161], s[38:39] op_sel_hi:[1,1,0]
	s_nop 0
	v_pk_fma_f32 v[126:127], v[126:127], v[160:161], s[40:41] op_sel_hi:[1,1,0]
	s_nop 0
	v_pk_mul_f32 v[124:125], v[124:125], v[126:127]
	s_nop 0
	v_pk_fma_f32 v[116:117], v[116:117], v[124:125], v[116:117]
	v_pk_mul_f32 v[124:125], v[118:119], s[16:17] op_sel_hi:[1,0]
	v_pk_mul_f32 v[118:119], v[118:119], 0.5 op_sel_hi:[1,0]
	v_med3_f32 v124, v124, s70, v173
	v_med3_f32 v125, v125, s70, v173
	v_pk_mul_f32 v[126:127], v[124:125], v[124:125]
	s_nop 0
	v_pk_fma_f32 v[160:161], v[126:127], s[18:19], v[158:159] op_sel_hi:[1,0,0] neg_lo:[1,0,0] neg_hi:[1,0,0]
	s_nop 0
	v_pk_fma_f32 v[160:161], v[126:127], v[160:161], s[28:29] op_sel_hi:[1,1,0]
	s_nop 0
	v_pk_fma_f32 v[160:161], v[126:127], v[160:161], s[30:31] op_sel_hi:[1,1,0]
	s_nop 0
	v_pk_fma_f32 v[160:161], v[126:127], v[160:161], s[34:35] op_sel_hi:[1,1,0]
	s_nop 0
	v_pk_fma_f32 v[160:161], v[126:127], v[160:161], s[36:37] op_sel_hi:[1,1,0]
	s_nop 0
	v_pk_fma_f32 v[160:161], v[126:127], v[160:161], s[38:39] op_sel_hi:[1,1,0]
	s_nop 0
	v_pk_fma_f32 v[126:127], v[126:127], v[160:161], s[40:41] op_sel_hi:[1,1,0]
	s_nop 0
	v_pk_mul_f32 v[124:125], v[124:125], v[126:127]
	s_nop 0
	v_pk_fma_f32 v[118:119], v[118:119], v[124:125], v[118:119]
	v_pk_mul_f32 v[124:125], v[112:113], s[16:17] op_sel_hi:[1,0]
	v_pk_mul_f32 v[112:113], v[112:113], 0.5 op_sel_hi:[1,0]
	v_med3_f32 v124, v124, s70, v173
	v_med3_f32 v125, v125, s70, v173
	v_pk_mul_f32 v[126:127], v[124:125], v[124:125]
	s_nop 0
	v_pk_fma_f32 v[160:161], v[126:127], s[18:19], v[158:159] op_sel_hi:[1,0,0] neg_lo:[1,0,0] neg_hi:[1,0,0]
	s_nop 0
	v_pk_fma_f32 v[160:161], v[126:127], v[160:161], s[28:29] op_sel_hi:[1,1,0]
	s_nop 0
	v_pk_fma_f32 v[160:161], v[126:127], v[160:161], s[30:31] op_sel_hi:[1,1,0]
	s_nop 0
	v_pk_fma_f32 v[160:161], v[126:127], v[160:161], s[34:35] op_sel_hi:[1,1,0]
	s_nop 0
	v_pk_fma_f32 v[160:161], v[126:127], v[160:161], s[36:37] op_sel_hi:[1,1,0]
	s_nop 0
	v_pk_fma_f32 v[160:161], v[126:127], v[160:161], s[38:39] op_sel_hi:[1,1,0]
	s_nop 0
	v_pk_fma_f32 v[126:127], v[126:127], v[160:161], s[40:41] op_sel_hi:[1,1,0]
	s_nop 0
	v_pk_mul_f32 v[124:125], v[124:125], v[126:127]
	s_nop 0
	v_pk_fma_f32 v[112:113], v[112:113], v[124:125], v[112:113]
	v_pk_mul_f32 v[124:125], v[114:115], s[16:17] op_sel_hi:[1,0]
	v_pk_mul_f32 v[114:115], v[114:115], 0.5 op_sel_hi:[1,0]
	v_med3_f32 v124, v124, s70, v173
	v_med3_f32 v125, v125, s70, v173
	v_pk_mul_f32 v[126:127], v[124:125], v[124:125]
	s_nop 0
	v_pk_fma_f32 v[158:159], v[126:127], s[18:19], v[158:159] op_sel_hi:[1,0,0] neg_lo:[1,0,0] neg_hi:[1,0,0]
	s_nop 0
	v_pk_fma_f32 v[158:159], v[126:127], v[158:159], s[28:29] op_sel_hi:[1,1,0]
	s_nop 0
	v_pk_fma_f32 v[158:159], v[126:127], v[158:159], s[30:31] op_sel_hi:[1,1,0]
	s_nop 0
	v_pk_fma_f32 v[158:159], v[126:127], v[158:159], s[34:35] op_sel_hi:[1,1,0]
	s_nop 0
	v_pk_fma_f32 v[158:159], v[126:127], v[158:159], s[36:37] op_sel_hi:[1,1,0]
	s_nop 0
	v_pk_fma_f32 v[158:159], v[126:127], v[158:159], s[38:39] op_sel_hi:[1,1,0]
	s_nop 0
	v_pk_fma_f32 v[126:127], v[126:127], v[158:159], s[40:41] op_sel_hi:[1,1,0]
	s_nop 0
	v_pk_mul_f32 v[124:125], v[124:125], v[126:127]
	s_nop 0
	v_pk_fma_f32 v[114:115], v[114:115], v[124:125], v[114:115]
; __device__ __forceinline__ unsigned cvt_pk_bf16(float lo, float hi) { unsigned r; asm volatile("v_cvt_pk_bf16_f32 %0, %1, %2" : "=v"(r) : "v"(lo), "v"(hi)); return r; }
; __device__ __forceinline__ f32x2 gelu_pk(f32x2 v) {
;     f32x2 x = v * 0.70710678118f;
;     x.x = __builtin_amdgcn_fmed3f(x.x, -2.9f, 2.9f); x.y = __builtin_amdgcn_fmed3f(x.y, -2.9f, 2.9f);
;     const f32x2 t = x * x;
;     f32x2 p = t * (-4.953124630e-07f) + 1.987094038e-05f;
;     p = p * t + (-3.472001117e-04f); p = p * t + 3.517547622e-03f; p = p * t + (-2.333305031e-02f); p = p * t + 1.087993085e-01f; p = p * t + (-3.740358949e-01f); p = p * t + 1.128076553e+00f;
;     const f32x2 hv = v * 0.5f;
;     return hv * (x * p) + hv;
; }
;     __device__ __forceinline__ void operator()(const f32x4 (&acc)[2][2][4][2], const Unit& u, int wr, int wc, int fr, int fq) const {
;     ...
;             for (int m = 0; m < 4; ++m) { bf16_t* rowp = O + (size_t)(row0 + ai * HALF + m * 16) * ldc + col0;
;                 const float rs = rsqrtf(rsv[ai][m] * (1.f / 1024.f) + 1e-6f);
; #pragma unroll
;                 for (int bj = 0; bj < 2; ++bj) if (bj == 0 || !u.q) { f32x4 v0 = acc[ai][bj][m][0] * rs, v1 = acc[ai][bj][m][1] * rs;
;                     if (act) { f32x2 a = gelu_pk((f32x2){v0[0], v0[1]}), b = gelu_pk((f32x2){v0[2], v0[3]}), c = gelu_pk((f32x2){v1[0], v1[1]}), d = gelu_pk((f32x2){v1[2], v1[3]});
;                         v0 = (f32x4){a.x, a.y, b.x, b.y}; v1 = (f32x4){c.x, c.y, d.x, d.y}; }
;                     u32x4 w; w.x = cvt_pk_bf16(v0[0], v0[1]); w.y = cvt_pk_bf16(v0[2], v0[3]); w.z = cvt_pk_bf16(v1[0], v1[1]); w.w = cvt_pk_bf16(v1[2], v1[3]);
;                     *(u32x4*)(rowp + bj * HALF) = w; } }
.LBB0_487:
	v_cvt_pk_bf16_f32 v116, v116, v117
	v_cvt_pk_bf16_f32 v117, v118, v119
	v_fmamk_f32 v118, v180, 0x3a800000, v172
	v_mul_f32_e32 v119, 0x4b800000, v118
	v_cmp_gt_f32_e32 vcc, s63, v118
	s_nop 1
	v_cndmask_b32_e32 v118, v118, v119, vcc
	v_rsq_f32_e32 v124, v118
	v_cvt_pk_bf16_f32 v118, v112, v113
	v_cvt_pk_bf16_f32 v119, v114, v115
	global_store_dwordx4 v[122:123], v[116:119], off offset:256 sc1
	v_mul_f32_e32 v112, 0x45800000, v124
	v_cndmask_b32_e32 v112, v124, v112, vcc
	v_pk_mul_f32 v[110:111], v[110:111], v[112:113] op_sel_hi:[1,0]
	v_pk_mul_f32 v[108:109], v[108:109], v[112:113] op_sel_hi:[1,0]
	v_pk_mul_f32 v[106:107], v[106:107], v[112:113] op_sel_hi:[1,0]
	s_and_b64 vcc, exec, s[10:11]
	v_pk_mul_f32 v[114:115], v[104:105], v[112:113] op_sel_hi:[1,0]
	s_cbranch_vccnz .LBB0_489
	v_pk_mul_f32 v[104:105], v[108:109], s[16:17] op_sel_hi:[1,0]
	v_mov_b64_e32 v[118:119], s[20:21]
	v_med3_f32 v104, v104, s70, v173
	v_med3_f32 v105, v105, s70, v173
	v_pk_mul_f32 v[116:117], v[104:105], v[104:105]
	v_pk_mul_f32 v[108:109], v[108:109], 0.5 op_sel_hi:[1,0]
	v_pk_fma_f32 v[122:123], v[116:117], s[18:19], v[118:119] op_sel_hi:[1,0,0] neg_lo:[1,0,0] neg_hi:[1,0,0]
	s_nop 0
	v_pk_fma_f32 v[122:123], v[116:117], v[122:123], s[28:29] op_sel_hi:[1,1,0]
	s_nop 0
	v_pk_fma_f32 v[122:123], v[116:117], v[122:123], s[30:31] op_sel_hi:[1,1,0]
	s_nop 0
	v_pk_fma_f32 v[122:123], v[116:117], v[122:123], s[34:35] op_sel_hi:[1,1,0]
	s_nop 0
	v_pk_fma_f32 v[122:123], v[116:117], v[122:123], s[36:37] op_sel_hi:[1,1,0]
	s_nop 0
	v_pk_fma_f32 v[122:123], v[116:117], v[122:123], s[38:39] op_sel_hi:[1,1,0]
	s_nop 0
	v_pk_fma_f32 v[116:117], v[116:117], v[122:123], s[40:41] op_sel_hi:[1,1,0]
	s_nop 0
	v_pk_mul_f32 v[104:105], v[104:105], v[116:117]
	s_nop 0
	v_pk_fma_f32 v[108:109], v[108:109], v[104:105], v[108:109]
	v_pk_mul_f32 v[104:105], v[110:111], s[16:17] op_sel_hi:[1,0]
	v_pk_mul_f32 v[110:111], v[110:111], 0.5 op_sel_hi:[1,0]
	v_med3_f32 v104, v104, s70, v173
	v_med3_f32 v105, v105, s70, v173
	v_pk_mul_f32 v[116:117], v[104:105], v[104:105]
	s_nop 0
	v_pk_fma_f32 v[122:123], v[116:117], s[18:19], v[118:119] op_sel_hi:[1,0,0] neg_lo:[1,0,0] neg_hi:[1,0,0]
	s_nop 0
	v_pk_fma_f32 v[122:123], v[116:117], v[122:123], s[28:29] op_sel_hi:[1,1,0]
	s_nop 0
	v_pk_fma_f32 v[122:123], v[116:117], v[122:123], s[30:31] op_sel_hi:[1,1,0]
	s_nop 0
	v_pk_fma_f32 v[122:123], v[116:117], v[122:123], s[34:35] op_sel_hi:[1,1,0]
	s_nop 0
	v_pk_fma_f32 v[122:123], v[116:117], v[122:123], s[36:37] op_sel_hi:[1,1,0]
	s_nop 0
	v_pk_fma_f32 v[122:123], v[116:117], v[122:123], s[38:39] op_sel_hi:[1,1,0]
	s_nop 0
	v_pk_fma_f32 v[116:117], v[116:117], v[122:123], s[40:41] op_sel_hi:[1,1,0]
	s_nop 0
	v_pk_mul_f32 v[104:105], v[104:105], v[116:117]
	s_nop 0
	v_pk_fma_f32 v[110:111], v[110:111], v[104:105], v[110:111]
	v_pk_mul_f32 v[104:105], v[114:115], s[16:17] op_sel_hi:[1,0]
	v_pk_mul_f32 v[114:115], v[114:115], 0.5 op_sel_hi:[1,0]
	v_med3_f32 v104, v104, s70, v173
	v_med3_f32 v105, v105, s70, v173
	v_pk_mul_f32 v[116:117], v[104:105], v[104:105]
	s_nop 0
	v_pk_fma_f32 v[122:123], v[116:117], s[18:19], v[118:119] op_sel_hi:[1,0,0] neg_lo:[1,0,0] neg_hi:[1,0,0]
	s_nop 0
	v_pk_fma_f32 v[122:123], v[116:117], v[122:123], s[28:29] op_sel_hi:[1,1,0]
	s_nop 0
	v_pk_fma_f32 v[122:123], v[116:117], v[122:123], s[30:31] op_sel_hi:[1,1,0]
	s_nop 0
	v_pk_fma_f32 v[122:123], v[116:117], v[122:123], s[34:35] op_sel_hi:[1,1,0]
	s_nop 0
	v_pk_fma_f32 v[122:123], v[116:117], v[122:123], s[36:37] op_sel_hi:[1,1,0]
	s_nop 0
	v_pk_fma_f32 v[122:123], v[116:117], v[122:123], s[38:39] op_sel_hi:[1,1,0]
	s_nop 0
	v_pk_fma_f32 v[116:117], v[116:117], v[122:123], s[40:41] op_sel_hi:[1,1,0]
	s_nop 0
	v_pk_mul_f32 v[104:105], v[104:105], v[116:117]
	s_nop 0
	v_pk_fma_f32 v[114:115], v[114:115], v[104:105], v[114:115]
	v_pk_mul_f32 v[104:105], v[106:107], s[16:17] op_sel_hi:[1,0]
	v_pk_mul_f32 v[106:107], v[106:107], 0.5 op_sel_hi:[1,0]
	v_med3_f32 v104, v104, s70, v173
	v_med3_f32 v105, v105, s70, v173
	v_pk_mul_f32 v[116:117], v[104:105], v[104:105]
	s_nop 0
	v_pk_fma_f32 v[118:119], v[116:117], s[18:19], v[118:119] op_sel_hi:[1,0,0] neg_lo:[1,0,0] neg_hi:[1,0,0]
	s_nop 0
	v_pk_fma_f32 v[118:119], v[116:117], v[118:119], s[28:29] op_sel_hi:[1,1,0]
	s_nop 0
	v_pk_fma_f32 v[118:119], v[116:117], v[118:119], s[30:31] op_sel_hi:[1,1,0]
	s_nop 0
	v_pk_fma_f32 v[118:119], v[116:117], v[118:119], s[34:35] op_sel_hi:[1,1,0]
	s_nop 0
	v_pk_fma_f32 v[118:119], v[116:117], v[118:119], s[36:37] op_sel_hi:[1,1,0]
	s_nop 0
	v_pk_fma_f32 v[118:119], v[116:117], v[118:119], s[38:39] op_sel_hi:[1,1,0]
	s_nop 0
	v_pk_fma_f32 v[116:117], v[116:117], v[118:119], s[40:41] op_sel_hi:[1,1,0]
	s_nop 0
	v_pk_mul_f32 v[104:105], v[104:105], v[116:117]
	s_nop 0
	v_pk_fma_f32 v[106:107], v[106:107], v[104:105], v[106:107]
; __device__ __forceinline__ unsigned cvt_pk_bf16(float lo, float hi) { unsigned r; asm volatile("v_cvt_pk_bf16_f32 %0, %1, %2" : "=v"(r) : "v"(lo), "v"(hi)); return r; }
; __device__ __forceinline__ f32x2 gelu_pk(f32x2 v) {
;     f32x2 x = v * 0.70710678118f;
;     x.x = __builtin_amdgcn_fmed3f(x.x, -2.9f, 2.9f); x.y = __builtin_amdgcn_fmed3f(x.y, -2.9f, 2.9f);
;     const f32x2 t = x * x;
;     f32x2 p = t * (-4.953124630e-07f) + 1.987094038e-05f;
;     p = p * t + (-3.472001117e-04f); p = p * t + 3.517547622e-03f; p = p * t + (-2.333305031e-02f); p = p * t + 1.087993085e-01f; p = p * t + (-3.740358949e-01f); p = p * t + 1.128076553e+00f;
;     const f32x2 hv = v * 0.5f;
;     return hv * (x * p) + hv;
; }
;     __device__ __forceinline__ void operator()(const f32x4 (&acc)[2][2][4][2], const Unit& u, int wr, int wc, int fr, int fq) const {
;     ...
;             for (int m = 0; m < 4; ++m) { bf16_t* rowp = O + (size_t)(row0 + ai * HALF + m * 16) * ldc + col0;
;                 const float rs = rsqrtf(rsv[ai][m] * (1.f / 1024.f) + 1e-6f);
; #pragma unroll
;                 for (int bj = 0; bj < 2; ++bj) if (bj == 0 || !u.q) { f32x4 v0 = acc[ai][bj][m][0] * rs, v1 = acc[ai][bj][m][1] * rs;
;                     if (act) { f32x2 a = gelu_pk((f32x2){v0[0], v0[1]}), b = gelu_pk((f32x2){v0[2], v0[3]}), c = gelu_pk((f32x2){v1[0], v1[1]}), d = gelu_pk((f32x2){v1[2], v1[3]});
;                         v0 = (f32x4){a.x, a.y, b.x, b.y}; v1 = (f32x4){c.x, c.y, d.x, d.y}; }
;                     u32x4 w; w.x = cvt_pk_bf16(v0[0], v0[1]); w.y = cvt_pk_bf16(v0[2], v0[3]); w.z = cvt_pk_bf16(v1[0], v1[1]); w.w = cvt_pk_bf16(v1[2], v1[3]);
;                     *(u32x4*)(rowp + bj * HALF) = w; } }
.LBB0_489:
	v_lshlrev_b64 v[104:105], 10, v[156:157]
	v_mov_b32_e32 v113, v112
	v_lshl_add_u64 v[104:105], s[64:65], 0, v[104:105]
	v_cvt_pk_bf16_f32 v108, v108, v109
	v_cvt_pk_bf16_f32 v109, v110, v111
	v_cvt_pk_bf16_f32 v110, v114, v115
	v_cvt_pk_bf16_f32 v111, v106, v107
	v_mov_b32_e32 v106, v112
	v_mov_b32_e32 v107, v112
	v_lshl_add_u64 v[104:105], v[120:121], 1, v[104:105]
	v_pk_mul_f32 v[102:103], v[102:103], v[106:107]
	v_pk_mul_f32 v[100:101], v[100:101], v[112:113]
	v_pk_mul_f32 v[98:99], v[98:99], v[106:107]
	s_and_b64 vcc, exec, s[10:11]
	v_pk_mul_f32 v[96:97], v[96:97], v[112:113]
	global_store_dwordx4 v[104:105], v[108:111], off sc1
	s_cbranch_vccnz .LBB0_491
	v_pk_mul_f32 v[106:107], v[100:101], s[16:17] op_sel_hi:[1,0]
	v_mov_b64_e32 v[110:111], s[20:21]
	v_med3_f32 v106, v106, s70, v173
	v_med3_f32 v107, v107, s70, v173
	v_pk_mul_f32 v[108:109], v[106:107], v[106:107]
	v_pk_mul_f32 v[100:101], v[100:101], 0.5 op_sel_hi:[1,0]
	v_pk_fma_f32 v[112:113], v[108:109], s[18:19], v[110:111] op_sel_hi:[1,0,0] neg_lo:[1,0,0] neg_hi:[1,0,0]
	s_nop 0
	v_pk_fma_f32 v[112:113], v[108:109], v[112:113], s[28:29] op_sel_hi:[1,1,0]
	s_nop 0
	v_pk_fma_f32 v[112:113], v[108:109], v[112:113], s[30:31] op_sel_hi:[1,1,0]
	s_nop 0
	v_pk_fma_f32 v[112:113], v[108:109], v[112:113], s[34:35] op_sel_hi:[1,1,0]
	s_nop 0
	v_pk_fma_f32 v[112:113], v[108:109], v[112:113], s[36:37] op_sel_hi:[1,1,0]
	s_nop 0
	v_pk_fma_f32 v[112:113], v[108:109], v[112:113], s[38:39] op_sel_hi:[1,1,0]
	s_nop 0
	v_pk_fma_f32 v[108:109], v[108:109], v[112:113], s[40:41] op_sel_hi:[1,1,0]
	s_nop 0
	v_pk_mul_f32 v[106:107], v[106:107], v[108:109]
	s_nop 0
	v_pk_fma_f32 v[100:101], v[100:101], v[106:107], v[100:101]
	v_pk_mul_f32 v[106:107], v[102:103], s[16:17] op_sel_hi:[1,0]
	v_pk_mul_f32 v[102:103], v[102:103], 0.5 op_sel_hi:[1,0]
	v_med3_f32 v106, v106, s70, v173
	v_med3_f32 v107, v107, s70, v173
	v_pk_mul_f32 v[108:109], v[106:107], v[106:107]
	s_nop 0
	v_pk_fma_f32 v[112:113], v[108:109], s[18:19], v[110:111] op_sel_hi:[1,0,0] neg_lo:[1,0,0] neg_hi:[1,0,0]
	s_nop 0
	v_pk_fma_f32 v[112:113], v[108:109], v[112:113], s[28:29] op_sel_hi:[1,1,0]
	s_nop 0
	v_pk_fma_f32 v[112:113], v[108:109], v[112:113], s[30:31] op_sel_hi:[1,1,0]
	s_nop 0
	v_pk_fma_f32 v[112:113], v[108:109], v[112:113], s[34:35] op_sel_hi:[1,1,0]
	s_nop 0
	v_pk_fma_f32 v[112:113], v[108:109], v[112:113], s[36:37] op_sel_hi:[1,1,0]
	s_nop 0
	v_pk_fma_f32 v[112:113], v[108:109], v[112:113], s[38:39] op_sel_hi:[1,1,0]
	s_nop 0
	v_pk_fma_f32 v[108:109], v[108:109], v[112:113], s[40:41] op_sel_hi:[1,1,0]
	s_nop 0
	v_pk_mul_f32 v[106:107], v[106:107], v[108:109]
	s_nop 0
	v_pk_fma_f32 v[102:103], v[102:103], v[106:107], v[102:103]
	v_pk_mul_f32 v[106:107], v[96:97], s[16:17] op_sel_hi:[1,0]
	v_pk_mul_f32 v[96:97], v[96:97], 0.5 op_sel_hi:[1,0]
	v_med3_f32 v106, v106, s70, v173
	v_med3_f32 v107, v107, s70, v173
	v_pk_mul_f32 v[108:109], v[106:107], v[106:107]
	s_nop 0
	v_pk_fma_f32 v[112:113], v[108:109], s[18:19], v[110:111] op_sel_hi:[1,0,0] neg_lo:[1,0,0] neg_hi:[1,0,0]
	s_nop 0
	v_pk_fma_f32 v[112:113], v[108:109], v[112:113], s[28:29] op_sel_hi:[1,1,0]
	s_nop 0
	v_pk_fma_f32 v[112:113], v[108:109], v[112:113], s[30:31] op_sel_hi:[1,1,0]
	s_nop 0
	v_pk_fma_f32 v[112:113], v[108:109], v[112:113], s[34:35] op_sel_hi:[1,1,0]
	s_nop 0
	v_pk_fma_f32 v[112:113], v[108:109], v[112:113], s[36:37] op_sel_hi:[1,1,0]
	s_nop 0
	v_pk_fma_f32 v[112:113], v[108:109], v[112:113], s[38:39] op_sel_hi:[1,1,0]
	s_nop 0
	v_pk_fma_f32 v[108:109], v[108:109], v[112:113], s[40:41] op_sel_hi:[1,1,0]
	s_nop 0
	v_pk_mul_f32 v[106:107], v[106:107], v[108:109]
	s_nop 0
	v_pk_fma_f32 v[96:97], v[96:97], v[106:107], v[96:97]
	v_pk_mul_f32 v[106:107], v[98:99], s[16:17] op_sel_hi:[1,0]
	v_pk_mul_f32 v[98:99], v[98:99], 0.5 op_sel_hi:[1,0]
	v_med3_f32 v106, v106, s70, v173
	v_med3_f32 v107, v107, s70, v173
	v_pk_mul_f32 v[108:109], v[106:107], v[106:107]
	s_nop 0
	v_pk_fma_f32 v[110:111], v[108:109], s[18:19], v[110:111] op_sel_hi:[1,0,0] neg_lo:[1,0,0] neg_hi:[1,0,0]
	s_nop 0
	v_pk_fma_f32 v[110:111], v[108:109], v[110:111], s[28:29] op_sel_hi:[1,1,0]
	s_nop 0
	v_pk_fma_f32 v[110:111], v[108:109], v[110:111], s[30:31] op_sel_hi:[1,1,0]
	s_nop 0
	v_pk_fma_f32 v[110:111], v[108:109], v[110:111], s[34:35] op_sel_hi:[1,1,0]
	s_nop 0
	v_pk_fma_f32 v[110:111], v[108:109], v[110:111], s[36:37] op_sel_hi:[1,1,0]
	s_nop 0
	v_pk_fma_f32 v[110:111], v[108:109], v[110:111], s[38:39] op_sel_hi:[1,1,0]
	s_nop 0
	v_pk_fma_f32 v[108:109], v[108:109], v[110:111], s[40:41] op_sel_hi:[1,1,0]
	s_nop 0
	v_pk_mul_f32 v[106:107], v[106:107], v[108:109]
	s_nop 0
	v_pk_fma_f32 v[98:99], v[98:99], v[106:107], v[98:99]
; __device__ __forceinline__ unsigned cvt_pk_bf16(float lo, float hi) { unsigned r; asm volatile("v_cvt_pk_bf16_f32 %0, %1, %2" : "=v"(r) : "v"(lo), "v"(hi)); return r; }
; __device__ __forceinline__ f32x2 gelu_pk(f32x2 v) {
;     f32x2 x = v * 0.70710678118f;
;     x.x = __builtin_amdgcn_fmed3f(x.x, -2.9f, 2.9f); x.y = __builtin_amdgcn_fmed3f(x.y, -2.9f, 2.9f);
;     const f32x2 t = x * x;
;     f32x2 p = t * (-4.953124630e-07f) + 1.987094038e-05f;
;     p = p * t + (-3.472001117e-04f); p = p * t + 3.517547622e-03f; p = p * t + (-2.333305031e-02f); p = p * t + 1.087993085e-01f; p = p * t + (-3.740358949e-01f); p = p * t + 1.128076553e+00f;
;     const f32x2 hv = v * 0.5f;
;     return hv * (x * p) + hv;
; }
;     __device__ __forceinline__ void operator()(const f32x4 (&acc)[2][2][4][2], const Unit& u, int wr, int wc, int fr, int fq) const {
;     ...
;             for (int m = 0; m < 4; ++m) { bf16_t* rowp = O + (size_t)(row0 + ai * HALF + m * 16) * ldc + col0;
;                 const float rs = rsqrtf(rsv[ai][m] * (1.f / 1024.f) + 1e-6f);
; #pragma unroll
;                 for (int bj = 0; bj < 2; ++bj) if (bj == 0 || !u.q) { f32x4 v0 = acc[ai][bj][m][0] * rs, v1 = acc[ai][bj][m][1] * rs;
;                     if (act) { f32x2 a = gelu_pk((f32x2){v0[0], v0[1]}), b = gelu_pk((f32x2){v0[2], v0[3]}), c = gelu_pk((f32x2){v1[0], v1[1]}), d = gelu_pk((f32x2){v1[2], v1[3]});
;                         v0 = (f32x4){a.x, a.y, b.x, b.y}; v1 = (f32x4){c.x, c.y, d.x, d.y}; }
;                     u32x4 w; w.x = cvt_pk_bf16(v0[0], v0[1]); w.y = cvt_pk_bf16(v0[2], v0[3]); w.z = cvt_pk_bf16(v1[0], v1[1]); w.w = cvt_pk_bf16(v1[2], v1[3]);
;                     *(u32x4*)(rowp + bj * HALF) = w; } }
.LBB0_491:
	v_cvt_pk_bf16_f32 v100, v100, v101
	v_cvt_pk_bf16_f32 v101, v102, v103
	v_fmamk_f32 v102, v179, 0x3a800000, v172
	v_mul_f32_e32 v103, 0x4b800000, v102
	v_cmp_gt_f32_e32 vcc, s63, v102
	s_nop 1
	v_cndmask_b32_e32 v102, v102, v103, vcc
	v_rsq_f32_e32 v106, v102
	v_cvt_pk_bf16_f32 v102, v96, v97
	v_cvt_pk_bf16_f32 v103, v98, v99
	global_store_dwordx4 v[104:105], v[100:103], off offset:256 sc1
	v_mul_f32_e32 v96, 0x45800000, v106
	v_cndmask_b32_e32 v96, v106, v96, vcc
	v_pk_mul_f32 v[94:95], v[94:95], v[96:97] op_sel_hi:[1,0]
	v_pk_mul_f32 v[92:93], v[92:93], v[96:97] op_sel_hi:[1,0]
	v_pk_mul_f32 v[90:91], v[90:91], v[96:97] op_sel_hi:[1,0]
	s_and_b64 vcc, exec, s[10:11]
	v_pk_mul_f32 v[98:99], v[88:89], v[96:97] op_sel_hi:[1,0]
	s_cbranch_vccnz .LBB0_493
	v_pk_mul_f32 v[88:89], v[92:93], s[16:17] op_sel_hi:[1,0]
	v_mov_b64_e32 v[102:103], s[20:21]
	v_med3_f32 v88, v88, s70, v173
	v_med3_f32 v89, v89, s70, v173
	v_pk_mul_f32 v[100:101], v[88:89], v[88:89]
	v_pk_mul_f32 v[92:93], v[92:93], 0.5 op_sel_hi:[1,0]
	v_pk_fma_f32 v[104:105], v[100:101], s[18:19], v[102:103] op_sel_hi:[1,0,0] neg_lo:[1,0,0] neg_hi:[1,0,0]
	s_nop 0
	v_pk_fma_f32 v[104:105], v[100:101], v[104:105], s[28:29] op_sel_hi:[1,1,0]
	s_nop 0
	v_pk_fma_f32 v[104:105], v[100:101], v[104:105], s[30:31] op_sel_hi:[1,1,0]
	s_nop 0
	v_pk_fma_f32 v[104:105], v[100:101], v[104:105], s[34:35] op_sel_hi:[1,1,0]
	s_nop 0
	v_pk_fma_f32 v[104:105], v[100:101], v[104:105], s[36:37] op_sel_hi:[1,1,0]
	s_nop 0
	v_pk_fma_f32 v[104:105], v[100:101], v[104:105], s[38:39] op_sel_hi:[1,1,0]
	s_nop 0
	v_pk_fma_f32 v[100:101], v[100:101], v[104:105], s[40:41] op_sel_hi:[1,1,0]
	s_nop 0
	v_pk_mul_f32 v[88:89], v[88:89], v[100:101]
	s_nop 0
	v_pk_fma_f32 v[92:93], v[92:93], v[88:89], v[92:93]
	v_pk_mul_f32 v[88:89], v[94:95], s[16:17] op_sel_hi:[1,0]
	v_pk_mul_f32 v[94:95], v[94:95], 0.5 op_sel_hi:[1,0]
	v_med3_f32 v88, v88, s70, v173
	v_med3_f32 v89, v89, s70, v173
	v_pk_mul_f32 v[100:101], v[88:89], v[88:89]
	s_nop 0
	v_pk_fma_f32 v[104:105], v[100:101], s[18:19], v[102:103] op_sel_hi:[1,0,0] neg_lo:[1,0,0] neg_hi:[1,0,0]
	s_nop 0
	v_pk_fma_f32 v[104:105], v[100:101], v[104:105], s[28:29] op_sel_hi:[1,1,0]
	s_nop 0
	v_pk_fma_f32 v[104:105], v[100:101], v[104:105], s[30:31] op_sel_hi:[1,1,0]
	s_nop 0
	v_pk_fma_f32 v[104:105], v[100:101], v[104:105], s[34:35] op_sel_hi:[1,1,0]
	s_nop 0
	v_pk_fma_f32 v[104:105], v[100:101], v[104:105], s[36:37] op_sel_hi:[1,1,0]
	s_nop 0
	v_pk_fma_f32 v[104:105], v[100:101], v[104:105], s[38:39] op_sel_hi:[1,1,0]
	s_nop 0
	v_pk_fma_f32 v[100:101], v[100:101], v[104:105], s[40:41] op_sel_hi:[1,1,0]
	s_nop 0
	v_pk_mul_f32 v[88:89], v[88:89], v[100:101]
	s_nop 0
	v_pk_fma_f32 v[94:95], v[94:95], v[88:89], v[94:95]
	v_pk_mul_f32 v[88:89], v[98:99], s[16:17] op_sel_hi:[1,0]
	v_pk_mul_f32 v[98:99], v[98:99], 0.5 op_sel_hi:[1,0]
	v_med3_f32 v88, v88, s70, v173
	v_med3_f32 v89, v89, s70, v173
	v_pk_mul_f32 v[100:101], v[88:89], v[88:89]
	s_nop 0
	v_pk_fma_f32 v[104:105], v[100:101], s[18:19], v[102:103] op_sel_hi:[1,0,0] neg_lo:[1,0,0] neg_hi:[1,0,0]
	s_nop 0
	v_pk_fma_f32 v[104:105], v[100:101], v[104:105], s[28:29] op_sel_hi:[1,1,0]
	s_nop 0
	v_pk_fma_f32 v[104:105], v[100:101], v[104:105], s[30:31] op_sel_hi:[1,1,0]
	s_nop 0
	v_pk_fma_f32 v[104:105], v[100:101], v[104:105], s[34:35] op_sel_hi:[1,1,0]
	s_nop 0
	v_pk_fma_f32 v[104:105], v[100:101], v[104:105], s[36:37] op_sel_hi:[1,1,0]
	s_nop 0
	v_pk_fma_f32 v[104:105], v[100:101], v[104:105], s[38:39] op_sel_hi:[1,1,0]
	s_nop 0
	v_pk_fma_f32 v[100:101], v[100:101], v[104:105], s[40:41] op_sel_hi:[1,1,0]
	s_nop 0
	v_pk_mul_f32 v[88:89], v[88:89], v[100:101]
	s_nop 0
	v_pk_fma_f32 v[98:99], v[98:99], v[88:89], v[98:99]
	v_pk_mul_f32 v[88:89], v[90:91], s[16:17] op_sel_hi:[1,0]
	v_pk_mul_f32 v[90:91], v[90:91], 0.5 op_sel_hi:[1,0]
	v_med3_f32 v88, v88, s70, v173
	v_med3_f32 v89, v89, s70, v173
	v_pk_mul_f32 v[100:101], v[88:89], v[88:89]
	s_nop 0
	v_pk_fma_f32 v[102:103], v[100:101], s[18:19], v[102:103] op_sel_hi:[1,0,0] neg_lo:[1,0,0] neg_hi:[1,0,0]
	s_nop 0
	v_pk_fma_f32 v[102:103], v[100:101], v[102:103], s[28:29] op_sel_hi:[1,1,0]
	s_nop 0
	v_pk_fma_f32 v[102:103], v[100:101], v[102:103], s[30:31] op_sel_hi:[1,1,0]
	s_nop 0
	v_pk_fma_f32 v[102:103], v[100:101], v[102:103], s[34:35] op_sel_hi:[1,1,0]
	s_nop 0
	v_pk_fma_f32 v[102:103], v[100:101], v[102:103], s[36:37] op_sel_hi:[1,1,0]
	s_nop 0
	v_pk_fma_f32 v[102:103], v[100:101], v[102:103], s[38:39] op_sel_hi:[1,1,0]
	s_nop 0
	v_pk_fma_f32 v[100:101], v[100:101], v[102:103], s[40:41] op_sel_hi:[1,1,0]
	s_nop 0
	v_pk_mul_f32 v[88:89], v[88:89], v[100:101]
	s_nop 0
	v_pk_fma_f32 v[90:91], v[90:91], v[88:89], v[90:91]
; __device__ __forceinline__ unsigned cvt_pk_bf16(float lo, float hi) { unsigned r; asm volatile("v_cvt_pk_bf16_f32 %0, %1, %2" : "=v"(r) : "v"(lo), "v"(hi)); return r; }
; __device__ __forceinline__ f32x2 gelu_pk(f32x2 v) {
;     f32x2 x = v * 0.70710678118f;
;     x.x = __builtin_amdgcn_fmed3f(x.x, -2.9f, 2.9f); x.y = __builtin_amdgcn_fmed3f(x.y, -2.9f, 2.9f);
;     const f32x2 t = x * x;
;     f32x2 p = t * (-4.953124630e-07f) + 1.987094038e-05f;
;     p = p * t + (-3.472001117e-04f); p = p * t + 3.517547622e-03f; p = p * t + (-2.333305031e-02f); p = p * t + 1.087993085e-01f; p = p * t + (-3.740358949e-01f); p = p * t + 1.128076553e+00f;
;     const f32x2 hv = v * 0.5f;
;     return hv * (x * p) + hv;
; }
;     __device__ __forceinline__ void operator()(const f32x4 (&acc)[2][2][4][2], const Unit& u, int wr, int wc, int fr, int fq) const {
;     ...
;             for (int m = 0; m < 4; ++m) { bf16_t* rowp = O + (size_t)(row0 + ai * HALF + m * 16) * ldc + col0;
;                 const float rs = rsqrtf(rsv[ai][m] * (1.f / 1024.f) + 1e-6f);
; #pragma unroll
;                 for (int bj = 0; bj < 2; ++bj) if (bj == 0 || !u.q) { f32x4 v0 = acc[ai][bj][m][0] * rs, v1 = acc[ai][bj][m][1] * rs;
;                     if (act) { f32x2 a = gelu_pk((f32x2){v0[0], v0[1]}), b = gelu_pk((f32x2){v0[2], v0[3]}), c = gelu_pk((f32x2){v1[0], v1[1]}), d = gelu_pk((f32x2){v1[2], v1[3]});
;                         v0 = (f32x4){a.x, a.y, b.x, b.y}; v1 = (f32x4){c.x, c.y, d.x, d.y}; }
;                     u32x4 w; w.x = cvt_pk_bf16(v0[0], v0[1]); w.y = cvt_pk_bf16(v0[2], v0[3]); w.z = cvt_pk_bf16(v1[0], v1[1]); w.w = cvt_pk_bf16(v1[2], v1[3]);
;                     *(u32x4*)(rowp + bj * HALF) = w; } }
.LBB0_493:
	v_lshlrev_b64 v[88:89], 10, v[154:155]
	v_mov_b32_e32 v97, v96
	v_lshl_add_u64 v[88:89], s[64:65], 0, v[88:89]
	v_cvt_pk_bf16_f32 v92, v92, v93
	v_cvt_pk_bf16_f32 v93, v94, v95
	v_cvt_pk_bf16_f32 v94, v98, v99
	v_cvt_pk_bf16_f32 v95, v90, v91
	v_mov_b32_e32 v90, v96
	v_mov_b32_e32 v91, v96
	v_lshl_add_u64 v[88:89], v[120:121], 1, v[88:89]
	v_pk_mul_f32 v[86:87], v[86:87], v[90:91]
	v_pk_mul_f32 v[84:85], v[84:85], v[96:97]
	v_pk_mul_f32 v[82:83], v[82:83], v[90:91]
	s_and_b64 vcc, exec, s[10:11]
	v_pk_mul_f32 v[80:81], v[80:81], v[96:97]
	global_store_dwordx4 v[88:89], v[92:95], off sc1
	s_cbranch_vccnz .LBB0_495
	v_pk_mul_f32 v[90:91], v[84:85], s[16:17] op_sel_hi:[1,0]
	v_mov_b64_e32 v[94:95], s[20:21]
	v_med3_f32 v90, v90, s70, v173
	v_med3_f32 v91, v91, s70, v173
	v_pk_mul_f32 v[92:93], v[90:91], v[90:91]
	v_pk_mul_f32 v[84:85], v[84:85], 0.5 op_sel_hi:[1,0]
	v_pk_fma_f32 v[96:97], v[92:93], s[18:19], v[94:95] op_sel_hi:[1,0,0] neg_lo:[1,0,0] neg_hi:[1,0,0]
	s_nop 0
	v_pk_fma_f32 v[96:97], v[92:93], v[96:97], s[28:29] op_sel_hi:[1,1,0]
	s_nop 0
	v_pk_fma_f32 v[96:97], v[92:93], v[96:97], s[30:31] op_sel_hi:[1,1,0]
	s_nop 0
	v_pk_fma_f32 v[96:97], v[92:93], v[96:97], s[34:35] op_sel_hi:[1,1,0]
	s_nop 0
	v_pk_fma_f32 v[96:97], v[92:93], v[96:97], s[36:37] op_sel_hi:[1,1,0]
	s_nop 0
	v_pk_fma_f32 v[96:97], v[92:93], v[96:97], s[38:39] op_sel_hi:[1,1,0]
	s_nop 0
	v_pk_fma_f32 v[92:93], v[92:93], v[96:97], s[40:41] op_sel_hi:[1,1,0]
	s_nop 0
	v_pk_mul_f32 v[90:91], v[90:91], v[92:93]
	s_nop 0
	v_pk_fma_f32 v[84:85], v[84:85], v[90:91], v[84:85]
	v_pk_mul_f32 v[90:91], v[86:87], s[16:17] op_sel_hi:[1,0]
	v_pk_mul_f32 v[86:87], v[86:87], 0.5 op_sel_hi:[1,0]
	v_med3_f32 v90, v90, s70, v173
	v_med3_f32 v91, v91, s70, v173
	v_pk_mul_f32 v[92:93], v[90:91], v[90:91]
	s_nop 0
	v_pk_fma_f32 v[96:97], v[92:93], s[18:19], v[94:95] op_sel_hi:[1,0,0] neg_lo:[1,0,0] neg_hi:[1,0,0]
	s_nop 0
	v_pk_fma_f32 v[96:97], v[92:93], v[96:97], s[28:29] op_sel_hi:[1,1,0]
	s_nop 0
	v_pk_fma_f32 v[96:97], v[92:93], v[96:97], s[30:31] op_sel_hi:[1,1,0]
	s_nop 0
	v_pk_fma_f32 v[96:97], v[92:93], v[96:97], s[34:35] op_sel_hi:[1,1,0]
	s_nop 0
	v_pk_fma_f32 v[96:97], v[92:93], v[96:97], s[36:37] op_sel_hi:[1,1,0]
	s_nop 0
	v_pk_fma_f32 v[96:97], v[92:93], v[96:97], s[38:39] op_sel_hi:[1,1,0]
	s_nop 0
	v_pk_fma_f32 v[92:93], v[92:93], v[96:97], s[40:41] op_sel_hi:[1,1,0]
	s_nop 0
	v_pk_mul_f32 v[90:91], v[90:91], v[92:93]
	s_nop 0
	v_pk_fma_f32 v[86:87], v[86:87], v[90:91], v[86:87]
	v_pk_mul_f32 v[90:91], v[80:81], s[16:17] op_sel_hi:[1,0]
	v_pk_mul_f32 v[80:81], v[80:81], 0.5 op_sel_hi:[1,0]
	v_med3_f32 v90, v90, s70, v173
	v_med3_f32 v91, v91, s70, v173
	v_pk_mul_f32 v[92:93], v[90:91], v[90:91]
	s_nop 0
	v_pk_fma_f32 v[96:97], v[92:93], s[18:19], v[94:95] op_sel_hi:[1,0,0] neg_lo:[1,0,0] neg_hi:[1,0,0]
	s_nop 0
	v_pk_fma_f32 v[96:97], v[92:93], v[96:97], s[28:29] op_sel_hi:[1,1,0]
	s_nop 0
	v_pk_fma_f32 v[96:97], v[92:93], v[96:97], s[30:31] op_sel_hi:[1,1,0]
	s_nop 0
	v_pk_fma_f32 v[96:97], v[92:93], v[96:97], s[34:35] op_sel_hi:[1,1,0]
	s_nop 0
	v_pk_fma_f32 v[96:97], v[92:93], v[96:97], s[36:37] op_sel_hi:[1,1,0]
	s_nop 0
	v_pk_fma_f32 v[96:97], v[92:93], v[96:97], s[38:39] op_sel_hi:[1,1,0]
	s_nop 0
	v_pk_fma_f32 v[92:93], v[92:93], v[96:97], s[40:41] op_sel_hi:[1,1,0]
	s_nop 0
	v_pk_mul_f32 v[90:91], v[90:91], v[92:93]
	s_nop 0
	v_pk_fma_f32 v[80:81], v[80:81], v[90:91], v[80:81]
	v_pk_mul_f32 v[90:91], v[82:83], s[16:17] op_sel_hi:[1,0]
	v_pk_mul_f32 v[82:83], v[82:83], 0.5 op_sel_hi:[1,0]
	v_med3_f32 v90, v90, s70, v173
	v_med3_f32 v91, v91, s70, v173
	v_pk_mul_f32 v[92:93], v[90:91], v[90:91]
	s_nop 0
	v_pk_fma_f32 v[94:95], v[92:93], s[18:19], v[94:95] op_sel_hi:[1,0,0] neg_lo:[1,0,0] neg_hi:[1,0,0]
	s_nop 0
	v_pk_fma_f32 v[94:95], v[92:93], v[94:95], s[28:29] op_sel_hi:[1,1,0]
	s_nop 0
	v_pk_fma_f32 v[94:95], v[92:93], v[94:95], s[30:31] op_sel_hi:[1,1,0]
	s_nop 0
	v_pk_fma_f32 v[94:95], v[92:93], v[94:95], s[34:35] op_sel_hi:[1,1,0]
	s_nop 0
	v_pk_fma_f32 v[94:95], v[92:93], v[94:95], s[36:37] op_sel_hi:[1,1,0]
	s_nop 0
	v_pk_fma_f32 v[94:95], v[92:93], v[94:95], s[38:39] op_sel_hi:[1,1,0]
	s_nop 0
	v_pk_fma_f32 v[92:93], v[92:93], v[94:95], s[40:41] op_sel_hi:[1,1,0]
	s_nop 0
	v_pk_mul_f32 v[90:91], v[90:91], v[92:93]
	s_nop 0
	v_pk_fma_f32 v[82:83], v[82:83], v[90:91], v[82:83]
; __device__ __forceinline__ unsigned cvt_pk_bf16(float lo, float hi) { unsigned r; asm volatile("v_cvt_pk_bf16_f32 %0, %1, %2" : "=v"(r) : "v"(lo), "v"(hi)); return r; }
; __device__ __forceinline__ f32x2 gelu_pk(f32x2 v) {
;     f32x2 x = v * 0.70710678118f;
;     x.x = __builtin_amdgcn_fmed3f(x.x, -2.9f, 2.9f); x.y = __builtin_amdgcn_fmed3f(x.y, -2.9f, 2.9f);
;     const f32x2 t = x * x;
;     f32x2 p = t * (-4.953124630e-07f) + 1.987094038e-05f;
;     p = p * t + (-3.472001117e-04f); p = p * t + 3.517547622e-03f; p = p * t + (-2.333305031e-02f); p = p * t + 1.087993085e-01f; p = p * t + (-3.740358949e-01f); p = p * t + 1.128076553e+00f;
;     const f32x2 hv = v * 0.5f;
;     return hv * (x * p) + hv;
; }
;     __device__ __forceinline__ void operator()(const f32x4 (&acc)[2][2][4][2], const Unit& u, int wr, int wc, int fr, int fq) const {
;     ...
;             for (int m = 0; m < 4; ++m) { bf16_t* rowp = O + (size_t)(row0 + ai * HALF + m * 16) * ldc + col0;
;                 const float rs = rsqrtf(rsv[ai][m] * (1.f / 1024.f) + 1e-6f);
; #pragma unroll
;                 for (int bj = 0; bj < 2; ++bj) if (bj == 0 || !u.q) { f32x4 v0 = acc[ai][bj][m][0] * rs, v1 = acc[ai][bj][m][1] * rs;
;                     if (act) { f32x2 a = gelu_pk((f32x2){v0[0], v0[1]}), b = gelu_pk((f32x2){v0[2], v0[3]}), c = gelu_pk((f32x2){v1[0], v1[1]}), d = gelu_pk((f32x2){v1[2], v1[3]});
;                         v0 = (f32x4){a.x, a.y, b.x, b.y}; v1 = (f32x4){c.x, c.y, d.x, d.y}; }
;                     u32x4 w; w.x = cvt_pk_bf16(v0[0], v0[1]); w.y = cvt_pk_bf16(v0[2], v0[3]); w.z = cvt_pk_bf16(v1[0], v1[1]); w.w = cvt_pk_bf16(v1[2], v1[3]);
;                     *(u32x4*)(rowp + bj * HALF) = w; } }
.LBB0_495:
	v_cvt_pk_bf16_f32 v84, v84, v85
	v_cvt_pk_bf16_f32 v85, v86, v87
	v_fmamk_f32 v86, v178, 0x3a800000, v172
	v_mul_f32_e32 v87, 0x4b800000, v86
	v_cmp_gt_f32_e32 vcc, s63, v86
	s_nop 1
	v_cndmask_b32_e32 v86, v86, v87, vcc
	v_rsq_f32_e32 v90, v86
	v_cvt_pk_bf16_f32 v86, v80, v81
	v_cvt_pk_bf16_f32 v87, v82, v83
	global_store_dwordx4 v[88:89], v[84:87], off offset:256 sc1
	v_mul_f32_e32 v80, 0x45800000, v90
	v_cndmask_b32_e32 v80, v90, v80, vcc
	v_pk_mul_f32 v[78:79], v[78:79], v[80:81] op_sel_hi:[1,0]
	v_pk_mul_f32 v[76:77], v[76:77], v[80:81] op_sel_hi:[1,0]
	v_pk_mul_f32 v[74:75], v[74:75], v[80:81] op_sel_hi:[1,0]
	s_and_b64 vcc, exec, s[10:11]
	v_pk_mul_f32 v[82:83], v[72:73], v[80:81] op_sel_hi:[1,0]
	s_cbranch_vccnz .LBB0_497
	v_pk_mul_f32 v[72:73], v[76:77], s[16:17] op_sel_hi:[1,0]
	v_mov_b64_e32 v[86:87], s[20:21]
	v_med3_f32 v72, v72, s70, v173
	v_med3_f32 v73, v73, s70, v173
	v_pk_mul_f32 v[84:85], v[72:73], v[72:73]
	v_pk_mul_f32 v[76:77], v[76:77], 0.5 op_sel_hi:[1,0]
	v_pk_fma_f32 v[88:89], v[84:85], s[18:19], v[86:87] op_sel_hi:[1,0,0] neg_lo:[1,0,0] neg_hi:[1,0,0]
	s_nop 0
	v_pk_fma_f32 v[88:89], v[84:85], v[88:89], s[28:29] op_sel_hi:[1,1,0]
	s_nop 0
	v_pk_fma_f32 v[88:89], v[84:85], v[88:89], s[30:31] op_sel_hi:[1,1,0]
	s_nop 0
	v_pk_fma_f32 v[88:89], v[84:85], v[88:89], s[34:35] op_sel_hi:[1,1,0]
	s_nop 0
	v_pk_fma_f32 v[88:89], v[84:85], v[88:89], s[36:37] op_sel_hi:[1,1,0]
	s_nop 0
	v_pk_fma_f32 v[88:89], v[84:85], v[88:89], s[38:39] op_sel_hi:[1,1,0]
	s_nop 0
	v_pk_fma_f32 v[84:85], v[84:85], v[88:89], s[40:41] op_sel_hi:[1,1,0]
	s_nop 0
	v_pk_mul_f32 v[72:73], v[72:73], v[84:85]
	s_nop 0
	v_pk_fma_f32 v[76:77], v[76:77], v[72:73], v[76:77]
	v_pk_mul_f32 v[72:73], v[78:79], s[16:17] op_sel_hi:[1,0]
	v_pk_mul_f32 v[78:79], v[78:79], 0.5 op_sel_hi:[1,0]
	v_med3_f32 v72, v72, s70, v173
	v_med3_f32 v73, v73, s70, v173
	v_pk_mul_f32 v[84:85], v[72:73], v[72:73]
	s_nop 0
	v_pk_fma_f32 v[88:89], v[84:85], s[18:19], v[86:87] op_sel_hi:[1,0,0] neg_lo:[1,0,0] neg_hi:[1,0,0]
	s_nop 0
	v_pk_fma_f32 v[88:89], v[84:85], v[88:89], s[28:29] op_sel_hi:[1,1,0]
	s_nop 0
	v_pk_fma_f32 v[88:89], v[84:85], v[88:89], s[30:31] op_sel_hi:[1,1,0]
	s_nop 0
	v_pk_fma_f32 v[88:89], v[84:85], v[88:89], s[34:35] op_sel_hi:[1,1,0]
	s_nop 0
	v_pk_fma_f32 v[88:89], v[84:85], v[88:89], s[36:37] op_sel_hi:[1,1,0]
	s_nop 0
	v_pk_fma_f32 v[88:89], v[84:85], v[88:89], s[38:39] op_sel_hi:[1,1,0]
	s_nop 0
	v_pk_fma_f32 v[84:85], v[84:85], v[88:89], s[40:41] op_sel_hi:[1,1,0]
	s_nop 0
	v_pk_mul_f32 v[72:73], v[72:73], v[84:85]
	s_nop 0
	v_pk_fma_f32 v[78:79], v[78:79], v[72:73], v[78:79]
	v_pk_mul_f32 v[72:73], v[82:83], s[16:17] op_sel_hi:[1,0]
	v_pk_mul_f32 v[82:83], v[82:83], 0.5 op_sel_hi:[1,0]
	v_med3_f32 v72, v72, s70, v173
	v_med3_f32 v73, v73, s70, v173
	v_pk_mul_f32 v[84:85], v[72:73], v[72:73]
	s_nop 0
	v_pk_fma_f32 v[88:89], v[84:85], s[18:19], v[86:87] op_sel_hi:[1,0,0] neg_lo:[1,0,0] neg_hi:[1,0,0]
	s_nop 0
	v_pk_fma_f32 v[88:89], v[84:85], v[88:89], s[28:29] op_sel_hi:[1,1,0]
	s_nop 0
	v_pk_fma_f32 v[88:89], v[84:85], v[88:89], s[30:31] op_sel_hi:[1,1,0]
	s_nop 0
	v_pk_fma_f32 v[88:89], v[84:85], v[88:89], s[34:35] op_sel_hi:[1,1,0]
	s_nop 0
	v_pk_fma_f32 v[88:89], v[84:85], v[88:89], s[36:37] op_sel_hi:[1,1,0]
	s_nop 0
	v_pk_fma_f32 v[88:89], v[84:85], v[88:89], s[38:39] op_sel_hi:[1,1,0]
	s_nop 0
	v_pk_fma_f32 v[84:85], v[84:85], v[88:89], s[40:41] op_sel_hi:[1,1,0]
	s_nop 0
	v_pk_mul_f32 v[72:73], v[72:73], v[84:85]
	s_nop 0
	v_pk_fma_f32 v[82:83], v[82:83], v[72:73], v[82:83]
	v_pk_mul_f32 v[72:73], v[74:75], s[16:17] op_sel_hi:[1,0]
	v_pk_mul_f32 v[74:75], v[74:75], 0.5 op_sel_hi:[1,0]
	v_med3_f32 v72, v72, s70, v173
	v_med3_f32 v73, v73, s70, v173
	v_pk_mul_f32 v[84:85], v[72:73], v[72:73]
	s_nop 0
	v_pk_fma_f32 v[86:87], v[84:85], s[18:19], v[86:87] op_sel_hi:[1,0,0] neg_lo:[1,0,0] neg_hi:[1,0,0]
	s_nop 0
	v_pk_fma_f32 v[86:87], v[84:85], v[86:87], s[28:29] op_sel_hi:[1,1,0]
	s_nop 0
	v_pk_fma_f32 v[86:87], v[84:85], v[86:87], s[30:31] op_sel_hi:[1,1,0]
	s_nop 0
	v_pk_fma_f32 v[86:87], v[84:85], v[86:87], s[34:35] op_sel_hi:[1,1,0]
	s_nop 0
	v_pk_fma_f32 v[86:87], v[84:85], v[86:87], s[36:37] op_sel_hi:[1,1,0]
	s_nop 0
	v_pk_fma_f32 v[86:87], v[84:85], v[86:87], s[38:39] op_sel_hi:[1,1,0]
	s_nop 0
	v_pk_fma_f32 v[84:85], v[84:85], v[86:87], s[40:41] op_sel_hi:[1,1,0]
	s_nop 0
	v_pk_mul_f32 v[72:73], v[72:73], v[84:85]
	s_nop 0
	v_pk_fma_f32 v[74:75], v[74:75], v[72:73], v[74:75]
; __device__ __forceinline__ unsigned cvt_pk_bf16(float lo, float hi) { unsigned r; asm volatile("v_cvt_pk_bf16_f32 %0, %1, %2" : "=v"(r) : "v"(lo), "v"(hi)); return r; }
; __device__ __forceinline__ f32x2 gelu_pk(f32x2 v) {
;     f32x2 x = v * 0.70710678118f;
;     x.x = __builtin_amdgcn_fmed3f(x.x, -2.9f, 2.9f); x.y = __builtin_amdgcn_fmed3f(x.y, -2.9f, 2.9f);
;     const f32x2 t = x * x;
;     f32x2 p = t * (-4.953124630e-07f) + 1.987094038e-05f;
;     p = p * t + (-3.472001117e-04f); p = p * t + 3.517547622e-03f; p = p * t + (-2.333305031e-02f); p = p * t + 1.087993085e-01f; p = p * t + (-3.740358949e-01f); p = p * t + 1.128076553e+00f;
;     const f32x2 hv = v * 0.5f;
;     return hv * (x * p) + hv;
; }
;     __device__ __forceinline__ void operator()(const f32x4 (&acc)[2][2][4][2], const Unit& u, int wr, int wc, int fr, int fq) const {
;     ...
;             for (int m = 0; m < 4; ++m) { bf16_t* rowp = O + (size_t)(row0 + ai * HALF + m * 16) * ldc + col0;
;                 const float rs = rsqrtf(rsv[ai][m] * (1.f / 1024.f) + 1e-6f);
; #pragma unroll
;                 for (int bj = 0; bj < 2; ++bj) if (bj == 0 || !u.q) { f32x4 v0 = acc[ai][bj][m][0] * rs, v1 = acc[ai][bj][m][1] * rs;
;                     if (act) { f32x2 a = gelu_pk((f32x2){v0[0], v0[1]}), b = gelu_pk((f32x2){v0[2], v0[3]}), c = gelu_pk((f32x2){v1[0], v1[1]}), d = gelu_pk((f32x2){v1[2], v1[3]});
;                         v0 = (f32x4){a.x, a.y, b.x, b.y}; v1 = (f32x4){c.x, c.y, d.x, d.y}; }
;                     u32x4 w; w.x = cvt_pk_bf16(v0[0], v0[1]); w.y = cvt_pk_bf16(v0[2], v0[3]); w.z = cvt_pk_bf16(v1[0], v1[1]); w.w = cvt_pk_bf16(v1[2], v1[3]);
;                     *(u32x4*)(rowp + bj * HALF) = w; } }
.LBB0_497:
	v_lshlrev_b64 v[72:73], 10, v[152:153]
	v_mov_b32_e32 v81, v80
	v_lshl_add_u64 v[72:73], s[64:65], 0, v[72:73]
	v_cvt_pk_bf16_f32 v76, v76, v77
	v_cvt_pk_bf16_f32 v77, v78, v79
	v_cvt_pk_bf16_f32 v78, v82, v83
	v_cvt_pk_bf16_f32 v79, v74, v75
	v_mov_b32_e32 v74, v80
	v_mov_b32_e32 v75, v80
	v_lshl_add_u64 v[72:73], v[120:121], 1, v[72:73]
	v_pk_mul_f32 v[70:71], v[70:71], v[74:75]
	v_pk_mul_f32 v[68:69], v[68:69], v[80:81]
	v_pk_mul_f32 v[66:67], v[66:67], v[74:75]
	s_and_b64 vcc, exec, s[10:11]
	v_pk_mul_f32 v[64:65], v[64:65], v[80:81]
	global_store_dwordx4 v[72:73], v[76:79], off sc1
	s_cbranch_vccnz .LBB0_499
	v_pk_mul_f32 v[74:75], v[68:69], s[16:17] op_sel_hi:[1,0]
	v_mov_b64_e32 v[78:79], s[20:21]
	v_med3_f32 v74, v74, s70, v173
	v_med3_f32 v75, v75, s70, v173
	v_pk_mul_f32 v[76:77], v[74:75], v[74:75]
	v_pk_mul_f32 v[68:69], v[68:69], 0.5 op_sel_hi:[1,0]
	v_pk_fma_f32 v[80:81], v[76:77], s[18:19], v[78:79] op_sel_hi:[1,0,0] neg_lo:[1,0,0] neg_hi:[1,0,0]
	s_nop 0
	v_pk_fma_f32 v[80:81], v[76:77], v[80:81], s[28:29] op_sel_hi:[1,1,0]
	s_nop 0
	v_pk_fma_f32 v[80:81], v[76:77], v[80:81], s[30:31] op_sel_hi:[1,1,0]
	s_nop 0
	v_pk_fma_f32 v[80:81], v[76:77], v[80:81], s[34:35] op_sel_hi:[1,1,0]
	s_nop 0
	v_pk_fma_f32 v[80:81], v[76:77], v[80:81], s[36:37] op_sel_hi:[1,1,0]
	s_nop 0
	v_pk_fma_f32 v[80:81], v[76:77], v[80:81], s[38:39] op_sel_hi:[1,1,0]
	s_nop 0
	v_pk_fma_f32 v[76:77], v[76:77], v[80:81], s[40:41] op_sel_hi:[1,1,0]
	s_nop 0
	v_pk_mul_f32 v[74:75], v[74:75], v[76:77]
	s_nop 0
	v_pk_fma_f32 v[68:69], v[68:69], v[74:75], v[68:69]
	v_pk_mul_f32 v[74:75], v[70:71], s[16:17] op_sel_hi:[1,0]
	v_pk_mul_f32 v[70:71], v[70:71], 0.5 op_sel_hi:[1,0]
	v_med3_f32 v74, v74, s70, v173
	v_med3_f32 v75, v75, s70, v173
	v_pk_mul_f32 v[76:77], v[74:75], v[74:75]
	s_nop 0
	v_pk_fma_f32 v[80:81], v[76:77], s[18:19], v[78:79] op_sel_hi:[1,0,0] neg_lo:[1,0,0] neg_hi:[1,0,0]
	s_nop 0
	v_pk_fma_f32 v[80:81], v[76:77], v[80:81], s[28:29] op_sel_hi:[1,1,0]
	s_nop 0
	v_pk_fma_f32 v[80:81], v[76:77], v[80:81], s[30:31] op_sel_hi:[1,1,0]
	s_nop 0
	v_pk_fma_f32 v[80:81], v[76:77], v[80:81], s[34:35] op_sel_hi:[1,1,0]
	s_nop 0
	v_pk_fma_f32 v[80:81], v[76:77], v[80:81], s[36:37] op_sel_hi:[1,1,0]
	s_nop 0
	v_pk_fma_f32 v[80:81], v[76:77], v[80:81], s[38:39] op_sel_hi:[1,1,0]
	s_nop 0
	v_pk_fma_f32 v[76:77], v[76:77], v[80:81], s[40:41] op_sel_hi:[1,1,0]
	s_nop 0
	v_pk_mul_f32 v[74:75], v[74:75], v[76:77]
	s_nop 0
	v_pk_fma_f32 v[70:71], v[70:71], v[74:75], v[70:71]
	v_pk_mul_f32 v[74:75], v[64:65], s[16:17] op_sel_hi:[1,0]
	v_pk_mul_f32 v[64:65], v[64:65], 0.5 op_sel_hi:[1,0]
	v_med3_f32 v74, v74, s70, v173
	v_med3_f32 v75, v75, s70, v173
	v_pk_mul_f32 v[76:77], v[74:75], v[74:75]
	s_nop 0
	v_pk_fma_f32 v[80:81], v[76:77], s[18:19], v[78:79] op_sel_hi:[1,0,0] neg_lo:[1,0,0] neg_hi:[1,0,0]
	s_nop 0
	v_pk_fma_f32 v[80:81], v[76:77], v[80:81], s[28:29] op_sel_hi:[1,1,0]
	s_nop 0
	v_pk_fma_f32 v[80:81], v[76:77], v[80:81], s[30:31] op_sel_hi:[1,1,0]
	s_nop 0
	v_pk_fma_f32 v[80:81], v[76:77], v[80:81], s[34:35] op_sel_hi:[1,1,0]
	s_nop 0
	v_pk_fma_f32 v[80:81], v[76:77], v[80:81], s[36:37] op_sel_hi:[1,1,0]
	s_nop 0
	v_pk_fma_f32 v[80:81], v[76:77], v[80:81], s[38:39] op_sel_hi:[1,1,0]
	s_nop 0
	v_pk_fma_f32 v[76:77], v[76:77], v[80:81], s[40:41] op_sel_hi:[1,1,0]
	s_nop 0
	v_pk_mul_f32 v[74:75], v[74:75], v[76:77]
	s_nop 0
	v_pk_fma_f32 v[64:65], v[64:65], v[74:75], v[64:65]
	v_pk_mul_f32 v[74:75], v[66:67], s[16:17] op_sel_hi:[1,0]
	v_pk_mul_f32 v[66:67], v[66:67], 0.5 op_sel_hi:[1,0]
	v_med3_f32 v74, v74, s70, v173
	v_med3_f32 v75, v75, s70, v173
	v_pk_mul_f32 v[76:77], v[74:75], v[74:75]
	s_nop 0
	v_pk_fma_f32 v[78:79], v[76:77], s[18:19], v[78:79] op_sel_hi:[1,0,0] neg_lo:[1,0,0] neg_hi:[1,0,0]
	s_nop 0
	v_pk_fma_f32 v[78:79], v[76:77], v[78:79], s[28:29] op_sel_hi:[1,1,0]
	s_nop 0
	v_pk_fma_f32 v[78:79], v[76:77], v[78:79], s[30:31] op_sel_hi:[1,1,0]
	s_nop 0
	v_pk_fma_f32 v[78:79], v[76:77], v[78:79], s[34:35] op_sel_hi:[1,1,0]
	s_nop 0
	v_pk_fma_f32 v[78:79], v[76:77], v[78:79], s[36:37] op_sel_hi:[1,1,0]
	s_nop 0
	v_pk_fma_f32 v[78:79], v[76:77], v[78:79], s[38:39] op_sel_hi:[1,1,0]
	s_nop 0
	v_pk_fma_f32 v[76:77], v[76:77], v[78:79], s[40:41] op_sel_hi:[1,1,0]
	s_nop 0
	v_pk_mul_f32 v[74:75], v[74:75], v[76:77]
	s_nop 0
	v_pk_fma_f32 v[66:67], v[66:67], v[74:75], v[66:67]
; __device__ __forceinline__ unsigned cvt_pk_bf16(float lo, float hi) { unsigned r; asm volatile("v_cvt_pk_bf16_f32 %0, %1, %2" : "=v"(r) : "v"(lo), "v"(hi)); return r; }
; __device__ __forceinline__ f32x2 gelu_pk(f32x2 v) {
;     f32x2 x = v * 0.70710678118f;
;     x.x = __builtin_amdgcn_fmed3f(x.x, -2.9f, 2.9f); x.y = __builtin_amdgcn_fmed3f(x.y, -2.9f, 2.9f);
;     const f32x2 t = x * x;
;     f32x2 p = t * (-4.953124630e-07f) + 1.987094038e-05f;
;     p = p * t + (-3.472001117e-04f); p = p * t + 3.517547622e-03f; p = p * t + (-2.333305031e-02f); p = p * t + 1.087993085e-01f; p = p * t + (-3.740358949e-01f); p = p * t + 1.128076553e+00f;
;     const f32x2 hv = v * 0.5f;
;     return hv * (x * p) + hv;
; }
;     __device__ __forceinline__ void operator()(const f32x4 (&acc)[2][2][4][2], const Unit& u, int wr, int wc, int fr, int fq) const {
;     ...
;             for (int m = 0; m < 4; ++m) { bf16_t* rowp = O + (size_t)(row0 + ai * HALF + m * 16) * ldc + col0;
;                 const float rs = rsqrtf(rsv[ai][m] * (1.f / 1024.f) + 1e-6f);
; #pragma unroll
;                 for (int bj = 0; bj < 2; ++bj) if (bj == 0 || !u.q) { f32x4 v0 = acc[ai][bj][m][0] * rs, v1 = acc[ai][bj][m][1] * rs;
;                     if (act) { f32x2 a = gelu_pk((f32x2){v0[0], v0[1]}), b = gelu_pk((f32x2){v0[2], v0[3]}), c = gelu_pk((f32x2){v1[0], v1[1]}), d = gelu_pk((f32x2){v1[2], v1[3]});
;                         v0 = (f32x4){a.x, a.y, b.x, b.y}; v1 = (f32x4){c.x, c.y, d.x, d.y}; }
;                     u32x4 w; w.x = cvt_pk_bf16(v0[0], v0[1]); w.y = cvt_pk_bf16(v0[2], v0[3]); w.z = cvt_pk_bf16(v1[0], v1[1]); w.w = cvt_pk_bf16(v1[2], v1[3]);
;                     *(u32x4*)(rowp + bj * HALF) = w; } }
.LBB0_499:
	v_cvt_pk_bf16_f32 v68, v68, v69
	v_cvt_pk_bf16_f32 v69, v70, v71
	v_fmamk_f32 v70, v177, 0x3a800000, v172
	v_mul_f32_e32 v71, 0x4b800000, v70
	v_cmp_gt_f32_e32 vcc, s63, v70
	s_nop 1
	v_cndmask_b32_e32 v70, v70, v71, vcc
	v_rsq_f32_e32 v74, v70
	v_cvt_pk_bf16_f32 v70, v64, v65
	v_cvt_pk_bf16_f32 v71, v66, v67
	global_store_dwordx4 v[72:73], v[68:71], off offset:256 sc1
	v_mul_f32_e32 v64, 0x45800000, v74
	v_cndmask_b32_e32 v64, v74, v64, vcc
	v_pk_mul_f32 v[62:63], v[62:63], v[64:65] op_sel_hi:[1,0]
	v_pk_mul_f32 v[60:61], v[60:61], v[64:65] op_sel_hi:[1,0]
	v_pk_mul_f32 v[58:59], v[58:59], v[64:65] op_sel_hi:[1,0]
	s_and_b64 vcc, exec, s[10:11]
	v_pk_mul_f32 v[66:67], v[56:57], v[64:65] op_sel_hi:[1,0]
	s_cbranch_vccnz .LBB0_501
	v_pk_mul_f32 v[56:57], v[60:61], s[16:17] op_sel_hi:[1,0]
	v_mov_b64_e32 v[70:71], s[20:21]
	v_med3_f32 v56, v56, s70, v173
	v_med3_f32 v57, v57, s70, v173
	v_pk_mul_f32 v[68:69], v[56:57], v[56:57]
	v_pk_mul_f32 v[60:61], v[60:61], 0.5 op_sel_hi:[1,0]
	v_pk_fma_f32 v[72:73], v[68:69], s[18:19], v[70:71] op_sel_hi:[1,0,0] neg_lo:[1,0,0] neg_hi:[1,0,0]
	s_nop 0
	v_pk_fma_f32 v[72:73], v[68:69], v[72:73], s[28:29] op_sel_hi:[1,1,0]
	s_nop 0
	v_pk_fma_f32 v[72:73], v[68:69], v[72:73], s[30:31] op_sel_hi:[1,1,0]
	s_nop 0
	v_pk_fma_f32 v[72:73], v[68:69], v[72:73], s[34:35] op_sel_hi:[1,1,0]
	s_nop 0
	v_pk_fma_f32 v[72:73], v[68:69], v[72:73], s[36:37] op_sel_hi:[1,1,0]
	s_nop 0
	v_pk_fma_f32 v[72:73], v[68:69], v[72:73], s[38:39] op_sel_hi:[1,1,0]
	s_nop 0
	v_pk_fma_f32 v[68:69], v[68:69], v[72:73], s[40:41] op_sel_hi:[1,1,0]
	s_nop 0
	v_pk_mul_f32 v[56:57], v[56:57], v[68:69]
	s_nop 0
	v_pk_fma_f32 v[60:61], v[60:61], v[56:57], v[60:61]
	v_pk_mul_f32 v[56:57], v[62:63], s[16:17] op_sel_hi:[1,0]
	v_pk_mul_f32 v[62:63], v[62:63], 0.5 op_sel_hi:[1,0]
	v_med3_f32 v56, v56, s70, v173
	v_med3_f32 v57, v57, s70, v173
	v_pk_mul_f32 v[68:69], v[56:57], v[56:57]
	s_nop 0
	v_pk_fma_f32 v[72:73], v[68:69], s[18:19], v[70:71] op_sel_hi:[1,0,0] neg_lo:[1,0,0] neg_hi:[1,0,0]
	s_nop 0
	v_pk_fma_f32 v[72:73], v[68:69], v[72:73], s[28:29] op_sel_hi:[1,1,0]
	s_nop 0
	v_pk_fma_f32 v[72:73], v[68:69], v[72:73], s[30:31] op_sel_hi:[1,1,0]
	s_nop 0
	v_pk_fma_f32 v[72:73], v[68:69], v[72:73], s[34:35] op_sel_hi:[1,1,0]
	s_nop 0
	v_pk_fma_f32 v[72:73], v[68:69], v[72:73], s[36:37] op_sel_hi:[1,1,0]
	s_nop 0
	v_pk_fma_f32 v[72:73], v[68:69], v[72:73], s[38:39] op_sel_hi:[1,1,0]
	s_nop 0
	v_pk_fma_f32 v[68:69], v[68:69], v[72:73], s[40:41] op_sel_hi:[1,1,0]
	s_nop 0
	v_pk_mul_f32 v[56:57], v[56:57], v[68:69]
	s_nop 0
	v_pk_fma_f32 v[62:63], v[62:63], v[56:57], v[62:63]
	v_pk_mul_f32 v[56:57], v[66:67], s[16:17] op_sel_hi:[1,0]
	v_pk_mul_f32 v[66:67], v[66:67], 0.5 op_sel_hi:[1,0]
	v_med3_f32 v56, v56, s70, v173
	v_med3_f32 v57, v57, s70, v173
	v_pk_mul_f32 v[68:69], v[56:57], v[56:57]
	s_nop 0
	v_pk_fma_f32 v[72:73], v[68:69], s[18:19], v[70:71] op_sel_hi:[1,0,0] neg_lo:[1,0,0] neg_hi:[1,0,0]
	s_nop 0
	v_pk_fma_f32 v[72:73], v[68:69], v[72:73], s[28:29] op_sel_hi:[1,1,0]
	s_nop 0
	v_pk_fma_f32 v[72:73], v[68:69], v[72:73], s[30:31] op_sel_hi:[1,1,0]
	s_nop 0
	v_pk_fma_f32 v[72:73], v[68:69], v[72:73], s[34:35] op_sel_hi:[1,1,0]
	s_nop 0
	v_pk_fma_f32 v[72:73], v[68:69], v[72:73], s[36:37] op_sel_hi:[1,1,0]
	s_nop 0
	v_pk_fma_f32 v[72:73], v[68:69], v[72:73], s[38:39] op_sel_hi:[1,1,0]
	s_nop 0
	v_pk_fma_f32 v[68:69], v[68:69], v[72:73], s[40:41] op_sel_hi:[1,1,0]
	s_nop 0
	v_pk_mul_f32 v[56:57], v[56:57], v[68:69]
	s_nop 0
	v_pk_fma_f32 v[66:67], v[66:67], v[56:57], v[66:67]
	v_pk_mul_f32 v[56:57], v[58:59], s[16:17] op_sel_hi:[1,0]
	v_pk_mul_f32 v[58:59], v[58:59], 0.5 op_sel_hi:[1,0]
	v_med3_f32 v56, v56, s70, v173
	v_med3_f32 v57, v57, s70, v173
	v_pk_mul_f32 v[68:69], v[56:57], v[56:57]
	s_nop 0
	v_pk_fma_f32 v[70:71], v[68:69], s[18:19], v[70:71] op_sel_hi:[1,0,0] neg_lo:[1,0,0] neg_hi:[1,0,0]
	s_nop 0
	v_pk_fma_f32 v[70:71], v[68:69], v[70:71], s[28:29] op_sel_hi:[1,1,0]
	s_nop 0
	v_pk_fma_f32 v[70:71], v[68:69], v[70:71], s[30:31] op_sel_hi:[1,1,0]
	s_nop 0
	v_pk_fma_f32 v[70:71], v[68:69], v[70:71], s[34:35] op_sel_hi:[1,1,0]
	s_nop 0
	v_pk_fma_f32 v[70:71], v[68:69], v[70:71], s[36:37] op_sel_hi:[1,1,0]
	s_nop 0
	v_pk_fma_f32 v[70:71], v[68:69], v[70:71], s[38:39] op_sel_hi:[1,1,0]
	s_nop 0
	v_pk_fma_f32 v[68:69], v[68:69], v[70:71], s[40:41] op_sel_hi:[1,1,0]
	s_nop 0
	v_pk_mul_f32 v[56:57], v[56:57], v[68:69]
	s_nop 0
	v_pk_fma_f32 v[58:59], v[58:59], v[56:57], v[58:59]
; __device__ __forceinline__ unsigned cvt_pk_bf16(float lo, float hi) { unsigned r; asm volatile("v_cvt_pk_bf16_f32 %0, %1, %2" : "=v"(r) : "v"(lo), "v"(hi)); return r; }
; __device__ __forceinline__ f32x2 gelu_pk(f32x2 v) {
;     f32x2 x = v * 0.70710678118f;
;     x.x = __builtin_amdgcn_fmed3f(x.x, -2.9f, 2.9f); x.y = __builtin_amdgcn_fmed3f(x.y, -2.9f, 2.9f);
;     const f32x2 t = x * x;
;     f32x2 p = t * (-4.953124630e-07f) + 1.987094038e-05f;
;     p = p * t + (-3.472001117e-04f); p = p * t + 3.517547622e-03f; p = p * t + (-2.333305031e-02f); p = p * t + 1.087993085e-01f; p = p * t + (-3.740358949e-01f); p = p * t + 1.128076553e+00f;
;     const f32x2 hv = v * 0.5f;
;     return hv * (x * p) + hv;
; }
;     __device__ __forceinline__ void operator()(const f32x4 (&acc)[2][2][4][2], const Unit& u, int wr, int wc, int fr, int fq) const {
;     ...
;             for (int m = 0; m < 4; ++m) { bf16_t* rowp = O + (size_t)(row0 + ai * HALF + m * 16) * ldc + col0;
;                 const float rs = rsqrtf(rsv[ai][m] * (1.f / 1024.f) + 1e-6f);
; #pragma unroll
;                 for (int bj = 0; bj < 2; ++bj) if (bj == 0 || !u.q) { f32x4 v0 = acc[ai][bj][m][0] * rs, v1 = acc[ai][bj][m][1] * rs;
;                     if (act) { f32x2 a = gelu_pk((f32x2){v0[0], v0[1]}), b = gelu_pk((f32x2){v0[2], v0[3]}), c = gelu_pk((f32x2){v1[0], v1[1]}), d = gelu_pk((f32x2){v1[2], v1[3]});
;                         v0 = (f32x4){a.x, a.y, b.x, b.y}; v1 = (f32x4){c.x, c.y, d.x, d.y}; }
;                     u32x4 w; w.x = cvt_pk_bf16(v0[0], v0[1]); w.y = cvt_pk_bf16(v0[2], v0[3]); w.z = cvt_pk_bf16(v1[0], v1[1]); w.w = cvt_pk_bf16(v1[2], v1[3]);
;                     *(u32x4*)(rowp + bj * HALF) = w; } }
.LBB0_501:
	v_lshlrev_b64 v[56:57], 10, v[150:151]
	v_mov_b32_e32 v65, v64
	v_lshl_add_u64 v[56:57], s[64:65], 0, v[56:57]
	v_cvt_pk_bf16_f32 v60, v60, v61
	v_cvt_pk_bf16_f32 v61, v62, v63
	v_cvt_pk_bf16_f32 v62, v66, v67
	v_cvt_pk_bf16_f32 v63, v58, v59
	v_mov_b32_e32 v58, v64
	v_mov_b32_e32 v59, v64
	v_lshl_add_u64 v[56:57], v[120:121], 1, v[56:57]
	v_pk_mul_f32 v[54:55], v[54:55], v[58:59]
	v_pk_mul_f32 v[52:53], v[52:53], v[64:65]
	v_pk_mul_f32 v[50:51], v[50:51], v[58:59]
	s_and_b64 vcc, exec, s[10:11]
	v_pk_mul_f32 v[48:49], v[48:49], v[64:65]
	global_store_dwordx4 v[56:57], v[60:63], off sc1
	s_cbranch_vccnz .LBB0_503
	v_pk_mul_f32 v[58:59], v[52:53], s[16:17] op_sel_hi:[1,0]
	v_mov_b64_e32 v[62:63], s[20:21]
	v_med3_f32 v58, v58, s70, v173
	v_med3_f32 v59, v59, s70, v173
	v_pk_mul_f32 v[60:61], v[58:59], v[58:59]
	v_pk_mul_f32 v[52:53], v[52:53], 0.5 op_sel_hi:[1,0]
	v_pk_fma_f32 v[64:65], v[60:61], s[18:19], v[62:63] op_sel_hi:[1,0,0] neg_lo:[1,0,0] neg_hi:[1,0,0]
	s_nop 0
	v_pk_fma_f32 v[64:65], v[60:61], v[64:65], s[28:29] op_sel_hi:[1,1,0]
	s_nop 0
	v_pk_fma_f32 v[64:65], v[60:61], v[64:65], s[30:31] op_sel_hi:[1,1,0]
	s_nop 0
	v_pk_fma_f32 v[64:65], v[60:61], v[64:65], s[34:35] op_sel_hi:[1,1,0]
	s_nop 0
	v_pk_fma_f32 v[64:65], v[60:61], v[64:65], s[36:37] op_sel_hi:[1,1,0]
	s_nop 0
	v_pk_fma_f32 v[64:65], v[60:61], v[64:65], s[38:39] op_sel_hi:[1,1,0]
	s_nop 0
	v_pk_fma_f32 v[60:61], v[60:61], v[64:65], s[40:41] op_sel_hi:[1,1,0]
	s_nop 0
	v_pk_mul_f32 v[58:59], v[58:59], v[60:61]
	s_nop 0
	v_pk_fma_f32 v[52:53], v[52:53], v[58:59], v[52:53]
	v_pk_mul_f32 v[58:59], v[54:55], s[16:17] op_sel_hi:[1,0]
	v_pk_mul_f32 v[54:55], v[54:55], 0.5 op_sel_hi:[1,0]
	v_med3_f32 v58, v58, s70, v173
	v_med3_f32 v59, v59, s70, v173
	v_pk_mul_f32 v[60:61], v[58:59], v[58:59]
	s_nop 0
	v_pk_fma_f32 v[64:65], v[60:61], s[18:19], v[62:63] op_sel_hi:[1,0,0] neg_lo:[1,0,0] neg_hi:[1,0,0]
	s_nop 0
	v_pk_fma_f32 v[64:65], v[60:61], v[64:65], s[28:29] op_sel_hi:[1,1,0]
	s_nop 0
	v_pk_fma_f32 v[64:65], v[60:61], v[64:65], s[30:31] op_sel_hi:[1,1,0]
	s_nop 0
	v_pk_fma_f32 v[64:65], v[60:61], v[64:65], s[34:35] op_sel_hi:[1,1,0]
	s_nop 0
	v_pk_fma_f32 v[64:65], v[60:61], v[64:65], s[36:37] op_sel_hi:[1,1,0]
	s_nop 0
	v_pk_fma_f32 v[64:65], v[60:61], v[64:65], s[38:39] op_sel_hi:[1,1,0]
	s_nop 0
	v_pk_fma_f32 v[60:61], v[60:61], v[64:65], s[40:41] op_sel_hi:[1,1,0]
	s_nop 0
	v_pk_mul_f32 v[58:59], v[58:59], v[60:61]
	s_nop 0
	v_pk_fma_f32 v[54:55], v[54:55], v[58:59], v[54:55]
	v_pk_mul_f32 v[58:59], v[48:49], s[16:17] op_sel_hi:[1,0]
	v_pk_mul_f32 v[48:49], v[48:49], 0.5 op_sel_hi:[1,0]
	v_med3_f32 v58, v58, s70, v173
	v_med3_f32 v59, v59, s70, v173
	v_pk_mul_f32 v[60:61], v[58:59], v[58:59]
	s_nop 0
	v_pk_fma_f32 v[64:65], v[60:61], s[18:19], v[62:63] op_sel_hi:[1,0,0] neg_lo:[1,0,0] neg_hi:[1,0,0]
	s_nop 0
	v_pk_fma_f32 v[64:65], v[60:61], v[64:65], s[28:29] op_sel_hi:[1,1,0]
	s_nop 0
	v_pk_fma_f32 v[64:65], v[60:61], v[64:65], s[30:31] op_sel_hi:[1,1,0]
	s_nop 0
	v_pk_fma_f32 v[64:65], v[60:61], v[64:65], s[34:35] op_sel_hi:[1,1,0]
	s_nop 0
	v_pk_fma_f32 v[64:65], v[60:61], v[64:65], s[36:37] op_sel_hi:[1,1,0]
	s_nop 0
	v_pk_fma_f32 v[64:65], v[60:61], v[64:65], s[38:39] op_sel_hi:[1,1,0]
	s_nop 0
	v_pk_fma_f32 v[60:61], v[60:61], v[64:65], s[40:41] op_sel_hi:[1,1,0]
	s_nop 0
	v_pk_mul_f32 v[58:59], v[58:59], v[60:61]
	s_nop 0
	v_pk_fma_f32 v[48:49], v[48:49], v[58:59], v[48:49]
	v_pk_mul_f32 v[58:59], v[50:51], s[16:17] op_sel_hi:[1,0]
	v_pk_mul_f32 v[50:51], v[50:51], 0.5 op_sel_hi:[1,0]
	v_med3_f32 v58, v58, s70, v173
	v_med3_f32 v59, v59, s70, v173
	v_pk_mul_f32 v[60:61], v[58:59], v[58:59]
	s_nop 0
	v_pk_fma_f32 v[62:63], v[60:61], s[18:19], v[62:63] op_sel_hi:[1,0,0] neg_lo:[1,0,0] neg_hi:[1,0,0]
	s_nop 0
	v_pk_fma_f32 v[62:63], v[60:61], v[62:63], s[28:29] op_sel_hi:[1,1,0]
	s_nop 0
	v_pk_fma_f32 v[62:63], v[60:61], v[62:63], s[30:31] op_sel_hi:[1,1,0]
	s_nop 0
	v_pk_fma_f32 v[62:63], v[60:61], v[62:63], s[34:35] op_sel_hi:[1,1,0]
	s_nop 0
	v_pk_fma_f32 v[62:63], v[60:61], v[62:63], s[36:37] op_sel_hi:[1,1,0]
	s_nop 0
	v_pk_fma_f32 v[62:63], v[60:61], v[62:63], s[38:39] op_sel_hi:[1,1,0]
	s_nop 0
	v_pk_fma_f32 v[60:61], v[60:61], v[62:63], s[40:41] op_sel_hi:[1,1,0]
	s_nop 0
	v_pk_mul_f32 v[58:59], v[58:59], v[60:61]
	s_nop 0
	v_pk_fma_f32 v[50:51], v[50:51], v[58:59], v[50:51]
; __device__ __forceinline__ unsigned cvt_pk_bf16(float lo, float hi) { unsigned r; asm volatile("v_cvt_pk_bf16_f32 %0, %1, %2" : "=v"(r) : "v"(lo), "v"(hi)); return r; }
; __device__ __forceinline__ f32x2 gelu_pk(f32x2 v) {
;     f32x2 x = v * 0.70710678118f;
;     x.x = __builtin_amdgcn_fmed3f(x.x, -2.9f, 2.9f); x.y = __builtin_amdgcn_fmed3f(x.y, -2.9f, 2.9f);
;     const f32x2 t = x * x;
;     f32x2 p = t * (-4.953124630e-07f) + 1.987094038e-05f;
;     p = p * t + (-3.472001117e-04f); p = p * t + 3.517547622e-03f; p = p * t + (-2.333305031e-02f); p = p * t + 1.087993085e-01f; p = p * t + (-3.740358949e-01f); p = p * t + 1.128076553e+00f;
;     const f32x2 hv = v * 0.5f;
;     return hv * (x * p) + hv;
; }
;     __device__ __forceinline__ void operator()(const f32x4 (&acc)[2][2][4][2], const Unit& u, int wr, int wc, int fr, int fq) const {
;     ...
;             for (int m = 0; m < 4; ++m) { bf16_t* rowp = O + (size_t)(row0 + ai * HALF + m * 16) * ldc + col0;
;                 const float rs = rsqrtf(rsv[ai][m] * (1.f / 1024.f) + 1e-6f);
; #pragma unroll
;                 for (int bj = 0; bj < 2; ++bj) if (bj == 0 || !u.q) { f32x4 v0 = acc[ai][bj][m][0] * rs, v1 = acc[ai][bj][m][1] * rs;
;                     if (act) { f32x2 a = gelu_pk((f32x2){v0[0], v0[1]}), b = gelu_pk((f32x2){v0[2], v0[3]}), c = gelu_pk((f32x2){v1[0], v1[1]}), d = gelu_pk((f32x2){v1[2], v1[3]});
;                         v0 = (f32x4){a.x, a.y, b.x, b.y}; v1 = (f32x4){c.x, c.y, d.x, d.y}; }
;                     u32x4 w; w.x = cvt_pk_bf16(v0[0], v0[1]); w.y = cvt_pk_bf16(v0[2], v0[3]); w.z = cvt_pk_bf16(v1[0], v1[1]); w.w = cvt_pk_bf16(v1[2], v1[3]);
;                     *(u32x4*)(rowp + bj * HALF) = w; } }
.LBB0_503:
	v_cvt_pk_bf16_f32 v52, v52, v53
	v_cvt_pk_bf16_f32 v53, v54, v55
	v_fmamk_f32 v54, v176, 0x3a800000, v172
	v_mul_f32_e32 v55, 0x4b800000, v54
	v_cmp_gt_f32_e32 vcc, s63, v54
	s_nop 1
	v_cndmask_b32_e32 v54, v54, v55, vcc
	v_rsq_f32_e32 v58, v54
	v_cvt_pk_bf16_f32 v54, v48, v49
	v_cvt_pk_bf16_f32 v55, v50, v51
	global_store_dwordx4 v[56:57], v[52:55], off offset:256 sc1
	v_mul_f32_e32 v48, 0x45800000, v58
	v_cndmask_b32_e32 v48, v58, v48, vcc
	v_pk_mul_f32 v[46:47], v[46:47], v[48:49] op_sel_hi:[1,0]
	v_pk_mul_f32 v[44:45], v[44:45], v[48:49] op_sel_hi:[1,0]
	v_pk_mul_f32 v[42:43], v[42:43], v[48:49] op_sel_hi:[1,0]
	s_and_b64 vcc, exec, s[10:11]
	v_pk_mul_f32 v[50:51], v[40:41], v[48:49] op_sel_hi:[1,0]
	s_cbranch_vccnz .LBB0_505
	v_pk_mul_f32 v[40:41], v[44:45], s[16:17] op_sel_hi:[1,0]
	v_mov_b64_e32 v[54:55], s[20:21]
	v_med3_f32 v40, v40, s70, v173
	v_med3_f32 v41, v41, s70, v173
	v_pk_mul_f32 v[52:53], v[40:41], v[40:41]
	v_pk_mul_f32 v[44:45], v[44:45], 0.5 op_sel_hi:[1,0]
	v_pk_fma_f32 v[56:57], v[52:53], s[18:19], v[54:55] op_sel_hi:[1,0,0] neg_lo:[1,0,0] neg_hi:[1,0,0]
	s_nop 0
	v_pk_fma_f32 v[56:57], v[52:53], v[56:57], s[28:29] op_sel_hi:[1,1,0]
	s_nop 0
	v_pk_fma_f32 v[56:57], v[52:53], v[56:57], s[30:31] op_sel_hi:[1,1,0]
	s_nop 0
	v_pk_fma_f32 v[56:57], v[52:53], v[56:57], s[34:35] op_sel_hi:[1,1,0]
	s_nop 0
	v_pk_fma_f32 v[56:57], v[52:53], v[56:57], s[36:37] op_sel_hi:[1,1,0]
	s_nop 0
	v_pk_fma_f32 v[56:57], v[52:53], v[56:57], s[38:39] op_sel_hi:[1,1,0]
	s_nop 0
	v_pk_fma_f32 v[52:53], v[52:53], v[56:57], s[40:41] op_sel_hi:[1,1,0]
	s_nop 0
	v_pk_mul_f32 v[40:41], v[40:41], v[52:53]
	s_nop 0
	v_pk_fma_f32 v[44:45], v[44:45], v[40:41], v[44:45]
	v_pk_mul_f32 v[40:41], v[46:47], s[16:17] op_sel_hi:[1,0]
	v_pk_mul_f32 v[46:47], v[46:47], 0.5 op_sel_hi:[1,0]
	v_med3_f32 v40, v40, s70, v173
	v_med3_f32 v41, v41, s70, v173
	v_pk_mul_f32 v[52:53], v[40:41], v[40:41]
	s_nop 0
	v_pk_fma_f32 v[56:57], v[52:53], s[18:19], v[54:55] op_sel_hi:[1,0,0] neg_lo:[1,0,0] neg_hi:[1,0,0]
	s_nop 0
	v_pk_fma_f32 v[56:57], v[52:53], v[56:57], s[28:29] op_sel_hi:[1,1,0]
	s_nop 0
	v_pk_fma_f32 v[56:57], v[52:53], v[56:57], s[30:31] op_sel_hi:[1,1,0]
	s_nop 0
	v_pk_fma_f32 v[56:57], v[52:53], v[56:57], s[34:35] op_sel_hi:[1,1,0]
	s_nop 0
	v_pk_fma_f32 v[56:57], v[52:53], v[56:57], s[36:37] op_sel_hi:[1,1,0]
	s_nop 0
	v_pk_fma_f32 v[56:57], v[52:53], v[56:57], s[38:39] op_sel_hi:[1,1,0]
	s_nop 0
	v_pk_fma_f32 v[52:53], v[52:53], v[56:57], s[40:41] op_sel_hi:[1,1,0]
	s_nop 0
	v_pk_mul_f32 v[40:41], v[40:41], v[52:53]
	s_nop 0
	v_pk_fma_f32 v[46:47], v[46:47], v[40:41], v[46:47]
	v_pk_mul_f32 v[40:41], v[50:51], s[16:17] op_sel_hi:[1,0]
	v_pk_mul_f32 v[50:51], v[50:51], 0.5 op_sel_hi:[1,0]
	v_med3_f32 v40, v40, s70, v173
	v_med3_f32 v41, v41, s70, v173
	v_pk_mul_f32 v[52:53], v[40:41], v[40:41]
	s_nop 0
	v_pk_fma_f32 v[56:57], v[52:53], s[18:19], v[54:55] op_sel_hi:[1,0,0] neg_lo:[1,0,0] neg_hi:[1,0,0]
	s_nop 0
	v_pk_fma_f32 v[56:57], v[52:53], v[56:57], s[28:29] op_sel_hi:[1,1,0]
	s_nop 0
	v_pk_fma_f32 v[56:57], v[52:53], v[56:57], s[30:31] op_sel_hi:[1,1,0]
	s_nop 0
	v_pk_fma_f32 v[56:57], v[52:53], v[56:57], s[34:35] op_sel_hi:[1,1,0]
	s_nop 0
	v_pk_fma_f32 v[56:57], v[52:53], v[56:57], s[36:37] op_sel_hi:[1,1,0]
	s_nop 0
	v_pk_fma_f32 v[56:57], v[52:53], v[56:57], s[38:39] op_sel_hi:[1,1,0]
	s_nop 0
	v_pk_fma_f32 v[52:53], v[52:53], v[56:57], s[40:41] op_sel_hi:[1,1,0]
	s_nop 0
	v_pk_mul_f32 v[40:41], v[40:41], v[52:53]
	s_nop 0
	v_pk_fma_f32 v[50:51], v[50:51], v[40:41], v[50:51]
	v_pk_mul_f32 v[40:41], v[42:43], s[16:17] op_sel_hi:[1,0]
	v_pk_mul_f32 v[42:43], v[42:43], 0.5 op_sel_hi:[1,0]
	v_med3_f32 v40, v40, s70, v173
	v_med3_f32 v41, v41, s70, v173
	v_pk_mul_f32 v[52:53], v[40:41], v[40:41]
	s_nop 0
	v_pk_fma_f32 v[54:55], v[52:53], s[18:19], v[54:55] op_sel_hi:[1,0,0] neg_lo:[1,0,0] neg_hi:[1,0,0]
	s_nop 0
	v_pk_fma_f32 v[54:55], v[52:53], v[54:55], s[28:29] op_sel_hi:[1,1,0]
	s_nop 0
	v_pk_fma_f32 v[54:55], v[52:53], v[54:55], s[30:31] op_sel_hi:[1,1,0]
	s_nop 0
	v_pk_fma_f32 v[54:55], v[52:53], v[54:55], s[34:35] op_sel_hi:[1,1,0]
	s_nop 0
	v_pk_fma_f32 v[54:55], v[52:53], v[54:55], s[36:37] op_sel_hi:[1,1,0]
	s_nop 0
	v_pk_fma_f32 v[54:55], v[52:53], v[54:55], s[38:39] op_sel_hi:[1,1,0]
	s_nop 0
	v_pk_fma_f32 v[52:53], v[52:53], v[54:55], s[40:41] op_sel_hi:[1,1,0]
	s_nop 0
	v_pk_mul_f32 v[40:41], v[40:41], v[52:53]
	s_nop 0
	v_pk_fma_f32 v[42:43], v[42:43], v[40:41], v[42:43]
; __device__ __forceinline__ unsigned cvt_pk_bf16(float lo, float hi) { unsigned r; asm volatile("v_cvt_pk_bf16_f32 %0, %1, %2" : "=v"(r) : "v"(lo), "v"(hi)); return r; }
; __device__ __forceinline__ f32x2 gelu_pk(f32x2 v) {
;     f32x2 x = v * 0.70710678118f;
;     x.x = __builtin_amdgcn_fmed3f(x.x, -2.9f, 2.9f); x.y = __builtin_amdgcn_fmed3f(x.y, -2.9f, 2.9f);
;     const f32x2 t = x * x;
;     f32x2 p = t * (-4.953124630e-07f) + 1.987094038e-05f;
;     p = p * t + (-3.472001117e-04f); p = p * t + 3.517547622e-03f; p = p * t + (-2.333305031e-02f); p = p * t + 1.087993085e-01f; p = p * t + (-3.740358949e-01f); p = p * t + 1.128076553e+00f;
;     const f32x2 hv = v * 0.5f;
;     return hv * (x * p) + hv;
; }
;     __device__ __forceinline__ void operator()(const f32x4 (&acc)[2][2][4][2], const Unit& u, int wr, int wc, int fr, int fq) const {
;     ...
;             for (int m = 0; m < 4; ++m) { bf16_t* rowp = O + (size_t)(row0 + ai * HALF + m * 16) * ldc + col0;
;                 const float rs = rsqrtf(rsv[ai][m] * (1.f / 1024.f) + 1e-6f);
; #pragma unroll
;                 for (int bj = 0; bj < 2; ++bj) if (bj == 0 || !u.q) { f32x4 v0 = acc[ai][bj][m][0] * rs, v1 = acc[ai][bj][m][1] * rs;
;                     if (act) { f32x2 a = gelu_pk((f32x2){v0[0], v0[1]}), b = gelu_pk((f32x2){v0[2], v0[3]}), c = gelu_pk((f32x2){v1[0], v1[1]}), d = gelu_pk((f32x2){v1[2], v1[3]});
;                         v0 = (f32x4){a.x, a.y, b.x, b.y}; v1 = (f32x4){c.x, c.y, d.x, d.y}; }
;                     u32x4 w; w.x = cvt_pk_bf16(v0[0], v0[1]); w.y = cvt_pk_bf16(v0[2], v0[3]); w.z = cvt_pk_bf16(v1[0], v1[1]); w.w = cvt_pk_bf16(v1[2], v1[3]);
;                     *(u32x4*)(rowp + bj * HALF) = w; } }
.LBB0_505:
	v_lshlrev_b64 v[40:41], 10, v[148:149]
	v_mov_b32_e32 v49, v48
	v_lshl_add_u64 v[40:41], s[64:65], 0, v[40:41]
	v_cvt_pk_bf16_f32 v44, v44, v45
	v_cvt_pk_bf16_f32 v45, v46, v47
	v_cvt_pk_bf16_f32 v46, v50, v51
	v_cvt_pk_bf16_f32 v47, v42, v43
	v_mov_b32_e32 v42, v48
	v_mov_b32_e32 v43, v48
	v_lshl_add_u64 v[40:41], v[120:121], 1, v[40:41]
	v_pk_mul_f32 v[38:39], v[38:39], v[42:43]
	v_pk_mul_f32 v[36:37], v[36:37], v[48:49]
	v_pk_mul_f32 v[34:35], v[34:35], v[42:43]
	s_and_b64 vcc, exec, s[10:11]
	v_pk_mul_f32 v[32:33], v[32:33], v[48:49]
	global_store_dwordx4 v[40:41], v[44:47], off sc1
	s_cbranch_vccnz .LBB0_507
	v_pk_mul_f32 v[42:43], v[36:37], s[16:17] op_sel_hi:[1,0]
	v_mov_b64_e32 v[46:47], s[20:21]
	v_med3_f32 v42, v42, s70, v173
	v_med3_f32 v43, v43, s70, v173
	v_pk_mul_f32 v[44:45], v[42:43], v[42:43]
	v_pk_mul_f32 v[36:37], v[36:37], 0.5 op_sel_hi:[1,0]
	v_pk_fma_f32 v[48:49], v[44:45], s[18:19], v[46:47] op_sel_hi:[1,0,0] neg_lo:[1,0,0] neg_hi:[1,0,0]
	s_nop 0
	v_pk_fma_f32 v[48:49], v[44:45], v[48:49], s[28:29] op_sel_hi:[1,1,0]
	s_nop 0
	v_pk_fma_f32 v[48:49], v[44:45], v[48:49], s[30:31] op_sel_hi:[1,1,0]
	s_nop 0
	v_pk_fma_f32 v[48:49], v[44:45], v[48:49], s[34:35] op_sel_hi:[1,1,0]
	s_nop 0
	v_pk_fma_f32 v[48:49], v[44:45], v[48:49], s[36:37] op_sel_hi:[1,1,0]
	s_nop 0
	v_pk_fma_f32 v[48:49], v[44:45], v[48:49], s[38:39] op_sel_hi:[1,1,0]
	s_nop 0
	v_pk_fma_f32 v[44:45], v[44:45], v[48:49], s[40:41] op_sel_hi:[1,1,0]
	s_nop 0
	v_pk_mul_f32 v[42:43], v[42:43], v[44:45]
	s_nop 0
	v_pk_fma_f32 v[36:37], v[36:37], v[42:43], v[36:37]
	v_pk_mul_f32 v[42:43], v[38:39], s[16:17] op_sel_hi:[1,0]
	v_pk_mul_f32 v[38:39], v[38:39], 0.5 op_sel_hi:[1,0]
	v_med3_f32 v42, v42, s70, v173
	v_med3_f32 v43, v43, s70, v173
	v_pk_mul_f32 v[44:45], v[42:43], v[42:43]
	s_nop 0
	v_pk_fma_f32 v[48:49], v[44:45], s[18:19], v[46:47] op_sel_hi:[1,0,0] neg_lo:[1,0,0] neg_hi:[1,0,0]
	s_nop 0
	v_pk_fma_f32 v[48:49], v[44:45], v[48:49], s[28:29] op_sel_hi:[1,1,0]
	s_nop 0
	v_pk_fma_f32 v[48:49], v[44:45], v[48:49], s[30:31] op_sel_hi:[1,1,0]
	s_nop 0
	v_pk_fma_f32 v[48:49], v[44:45], v[48:49], s[34:35] op_sel_hi:[1,1,0]
	s_nop 0
	v_pk_fma_f32 v[48:49], v[44:45], v[48:49], s[36:37] op_sel_hi:[1,1,0]
	s_nop 0
	v_pk_fma_f32 v[48:49], v[44:45], v[48:49], s[38:39] op_sel_hi:[1,1,0]
	s_nop 0
	v_pk_fma_f32 v[44:45], v[44:45], v[48:49], s[40:41] op_sel_hi:[1,1,0]
	s_nop 0
	v_pk_mul_f32 v[42:43], v[42:43], v[44:45]
	s_nop 0
	v_pk_fma_f32 v[38:39], v[38:39], v[42:43], v[38:39]
	v_pk_mul_f32 v[42:43], v[32:33], s[16:17] op_sel_hi:[1,0]
	v_pk_mul_f32 v[32:33], v[32:33], 0.5 op_sel_hi:[1,0]
	v_med3_f32 v42, v42, s70, v173
	v_med3_f32 v43, v43, s70, v173
	v_pk_mul_f32 v[44:45], v[42:43], v[42:43]
	s_nop 0
	v_pk_fma_f32 v[48:49], v[44:45], s[18:19], v[46:47] op_sel_hi:[1,0,0] neg_lo:[1,0,0] neg_hi:[1,0,0]
	s_nop 0
	v_pk_fma_f32 v[48:49], v[44:45], v[48:49], s[28:29] op_sel_hi:[1,1,0]
	s_nop 0
	v_pk_fma_f32 v[48:49], v[44:45], v[48:49], s[30:31] op_sel_hi:[1,1,0]
	s_nop 0
	v_pk_fma_f32 v[48:49], v[44:45], v[48:49], s[34:35] op_sel_hi:[1,1,0]
	s_nop 0
	v_pk_fma_f32 v[48:49], v[44:45], v[48:49], s[36:37] op_sel_hi:[1,1,0]
	s_nop 0
	v_pk_fma_f32 v[48:49], v[44:45], v[48:49], s[38:39] op_sel_hi:[1,1,0]
	s_nop 0
	v_pk_fma_f32 v[44:45], v[44:45], v[48:49], s[40:41] op_sel_hi:[1,1,0]
	s_nop 0
	v_pk_mul_f32 v[42:43], v[42:43], v[44:45]
	s_nop 0
	v_pk_fma_f32 v[32:33], v[32:33], v[42:43], v[32:33]
	v_pk_mul_f32 v[42:43], v[34:35], s[16:17] op_sel_hi:[1,0]
	v_pk_mul_f32 v[34:35], v[34:35], 0.5 op_sel_hi:[1,0]
	v_med3_f32 v42, v42, s70, v173
	v_med3_f32 v43, v43, s70, v173
	v_pk_mul_f32 v[44:45], v[42:43], v[42:43]
	s_nop 0
	v_pk_fma_f32 v[46:47], v[44:45], s[18:19], v[46:47] op_sel_hi:[1,0,0] neg_lo:[1,0,0] neg_hi:[1,0,0]
	s_nop 0
	v_pk_fma_f32 v[46:47], v[44:45], v[46:47], s[28:29] op_sel_hi:[1,1,0]
	s_nop 0
	v_pk_fma_f32 v[46:47], v[44:45], v[46:47], s[30:31] op_sel_hi:[1,1,0]
	s_nop 0
	v_pk_fma_f32 v[46:47], v[44:45], v[46:47], s[34:35] op_sel_hi:[1,1,0]
	s_nop 0
	v_pk_fma_f32 v[46:47], v[44:45], v[46:47], s[36:37] op_sel_hi:[1,1,0]
	s_nop 0
	v_pk_fma_f32 v[46:47], v[44:45], v[46:47], s[38:39] op_sel_hi:[1,1,0]
	s_nop 0
	v_pk_fma_f32 v[44:45], v[44:45], v[46:47], s[40:41] op_sel_hi:[1,1,0]
	s_nop 0
	v_pk_mul_f32 v[42:43], v[42:43], v[44:45]
	s_nop 0
	v_pk_fma_f32 v[34:35], v[34:35], v[42:43], v[34:35]
; __device__ __forceinline__ unsigned cvt_pk_bf16(float lo, float hi) { unsigned r; asm volatile("v_cvt_pk_bf16_f32 %0, %1, %2" : "=v"(r) : "v"(lo), "v"(hi)); return r; }
; __device__ __forceinline__ f32x2 gelu_pk(f32x2 v) {
;     f32x2 x = v * 0.70710678118f;
;     x.x = __builtin_amdgcn_fmed3f(x.x, -2.9f, 2.9f); x.y = __builtin_amdgcn_fmed3f(x.y, -2.9f, 2.9f);
;     const f32x2 t = x * x;
;     f32x2 p = t * (-4.953124630e-07f) + 1.987094038e-05f;
;     p = p * t + (-3.472001117e-04f); p = p * t + 3.517547622e-03f; p = p * t + (-2.333305031e-02f); p = p * t + 1.087993085e-01f; p = p * t + (-3.740358949e-01f); p = p * t + 1.128076553e+00f;
;     const f32x2 hv = v * 0.5f;
;     return hv * (x * p) + hv;
; }
;     __device__ __forceinline__ void operator()(const f32x4 (&acc)[2][2][4][2], const Unit& u, int wr, int wc, int fr, int fq) const {
;     ...
;             for (int m = 0; m < 4; ++m) { bf16_t* rowp = O + (size_t)(row0 + ai * HALF + m * 16) * ldc + col0;
;                 const float rs = rsqrtf(rsv[ai][m] * (1.f / 1024.f) + 1e-6f);
; #pragma unroll
;                 for (int bj = 0; bj < 2; ++bj) if (bj == 0 || !u.q) { f32x4 v0 = acc[ai][bj][m][0] * rs, v1 = acc[ai][bj][m][1] * rs;
;                     if (act) { f32x2 a = gelu_pk((f32x2){v0[0], v0[1]}), b = gelu_pk((f32x2){v0[2], v0[3]}), c = gelu_pk((f32x2){v1[0], v1[1]}), d = gelu_pk((f32x2){v1[2], v1[3]});
;                         v0 = (f32x4){a.x, a.y, b.x, b.y}; v1 = (f32x4){c.x, c.y, d.x, d.y}; }
;                     u32x4 w; w.x = cvt_pk_bf16(v0[0], v0[1]); w.y = cvt_pk_bf16(v0[2], v0[3]); w.z = cvt_pk_bf16(v1[0], v1[1]); w.w = cvt_pk_bf16(v1[2], v1[3]);
;                     *(u32x4*)(rowp + bj * HALF) = w; } }
.LBB0_507:
	v_cvt_pk_bf16_f32 v36, v36, v37
	v_cvt_pk_bf16_f32 v37, v38, v39
	v_fmamk_f32 v38, v175, 0x3a800000, v172
	v_mul_f32_e32 v39, 0x4b800000, v38
	v_cmp_gt_f32_e32 vcc, s63, v38
	s_nop 1
	v_cndmask_b32_e32 v38, v38, v39, vcc
	v_rsq_f32_e32 v42, v38
	v_cvt_pk_bf16_f32 v38, v32, v33
	v_cvt_pk_bf16_f32 v39, v34, v35
	global_store_dwordx4 v[40:41], v[36:39], off offset:256 sc1
	v_mul_f32_e32 v32, 0x45800000, v42
	v_cndmask_b32_e32 v32, v42, v32, vcc
	v_pk_mul_f32 v[30:31], v[30:31], v[32:33] op_sel_hi:[1,0]
	v_pk_mul_f32 v[28:29], v[28:29], v[32:33] op_sel_hi:[1,0]
	v_pk_mul_f32 v[26:27], v[26:27], v[32:33] op_sel_hi:[1,0]
	s_and_b64 vcc, exec, s[10:11]
	v_pk_mul_f32 v[34:35], v[24:25], v[32:33] op_sel_hi:[1,0]
	s_cbranch_vccnz .LBB0_509
	v_pk_mul_f32 v[24:25], v[28:29], s[16:17] op_sel_hi:[1,0]
	v_mov_b64_e32 v[38:39], s[20:21]
	v_med3_f32 v24, v24, s70, v173
	v_med3_f32 v25, v25, s70, v173
	v_pk_mul_f32 v[36:37], v[24:25], v[24:25]
	v_pk_mul_f32 v[28:29], v[28:29], 0.5 op_sel_hi:[1,0]
	v_pk_fma_f32 v[40:41], v[36:37], s[18:19], v[38:39] op_sel_hi:[1,0,0] neg_lo:[1,0,0] neg_hi:[1,0,0]
	s_nop 0
	v_pk_fma_f32 v[40:41], v[36:37], v[40:41], s[28:29] op_sel_hi:[1,1,0]
	s_nop 0
	v_pk_fma_f32 v[40:41], v[36:37], v[40:41], s[30:31] op_sel_hi:[1,1,0]
	s_nop 0
	v_pk_fma_f32 v[40:41], v[36:37], v[40:41], s[34:35] op_sel_hi:[1,1,0]
	s_nop 0
	v_pk_fma_f32 v[40:41], v[36:37], v[40:41], s[36:37] op_sel_hi:[1,1,0]
	s_nop 0
	v_pk_fma_f32 v[40:41], v[36:37], v[40:41], s[38:39] op_sel_hi:[1,1,0]
	s_nop 0
	v_pk_fma_f32 v[36:37], v[36:37], v[40:41], s[40:41] op_sel_hi:[1,1,0]
	s_nop 0
	v_pk_mul_f32 v[24:25], v[24:25], v[36:37]
	s_nop 0
	v_pk_fma_f32 v[28:29], v[28:29], v[24:25], v[28:29]
	v_pk_mul_f32 v[24:25], v[30:31], s[16:17] op_sel_hi:[1,0]
	v_pk_mul_f32 v[30:31], v[30:31], 0.5 op_sel_hi:[1,0]
	v_med3_f32 v24, v24, s70, v173
	v_med3_f32 v25, v25, s70, v173
	v_pk_mul_f32 v[36:37], v[24:25], v[24:25]
	s_nop 0
	v_pk_fma_f32 v[40:41], v[36:37], s[18:19], v[38:39] op_sel_hi:[1,0,0] neg_lo:[1,0,0] neg_hi:[1,0,0]
	s_nop 0
	v_pk_fma_f32 v[40:41], v[36:37], v[40:41], s[28:29] op_sel_hi:[1,1,0]
	s_nop 0
	v_pk_fma_f32 v[40:41], v[36:37], v[40:41], s[30:31] op_sel_hi:[1,1,0]
	s_nop 0
	v_pk_fma_f32 v[40:41], v[36:37], v[40:41], s[34:35] op_sel_hi:[1,1,0]
	s_nop 0
	v_pk_fma_f32 v[40:41], v[36:37], v[40:41], s[36:37] op_sel_hi:[1,1,0]
	s_nop 0
	v_pk_fma_f32 v[40:41], v[36:37], v[40:41], s[38:39] op_sel_hi:[1,1,0]
	s_nop 0
	v_pk_fma_f32 v[36:37], v[36:37], v[40:41], s[40:41] op_sel_hi:[1,1,0]
	s_nop 0
	v_pk_mul_f32 v[24:25], v[24:25], v[36:37]
	s_nop 0
	v_pk_fma_f32 v[30:31], v[30:31], v[24:25], v[30:31]
	v_pk_mul_f32 v[24:25], v[34:35], s[16:17] op_sel_hi:[1,0]
	v_pk_mul_f32 v[34:35], v[34:35], 0.5 op_sel_hi:[1,0]
	v_med3_f32 v24, v24, s70, v173
	v_med3_f32 v25, v25, s70, v173
	v_pk_mul_f32 v[36:37], v[24:25], v[24:25]
	s_nop 0
	v_pk_fma_f32 v[40:41], v[36:37], s[18:19], v[38:39] op_sel_hi:[1,0,0] neg_lo:[1,0,0] neg_hi:[1,0,0]
	s_nop 0
	v_pk_fma_f32 v[40:41], v[36:37], v[40:41], s[28:29] op_sel_hi:[1,1,0]
	s_nop 0
	v_pk_fma_f32 v[40:41], v[36:37], v[40:41], s[30:31] op_sel_hi:[1,1,0]
	s_nop 0
	v_pk_fma_f32 v[40:41], v[36:37], v[40:41], s[34:35] op_sel_hi:[1,1,0]
	s_nop 0
	v_pk_fma_f32 v[40:41], v[36:37], v[40:41], s[36:37] op_sel_hi:[1,1,0]
	s_nop 0
	v_pk_fma_f32 v[40:41], v[36:37], v[40:41], s[38:39] op_sel_hi:[1,1,0]
	s_nop 0
	v_pk_fma_f32 v[36:37], v[36:37], v[40:41], s[40:41] op_sel_hi:[1,1,0]
	s_nop 0
	v_pk_mul_f32 v[24:25], v[24:25], v[36:37]
	s_nop 0
	v_pk_fma_f32 v[34:35], v[34:35], v[24:25], v[34:35]
	v_pk_mul_f32 v[24:25], v[26:27], s[16:17] op_sel_hi:[1,0]
	v_pk_mul_f32 v[26:27], v[26:27], 0.5 op_sel_hi:[1,0]
	v_med3_f32 v24, v24, s70, v173
	v_med3_f32 v25, v25, s70, v173
	v_pk_mul_f32 v[36:37], v[24:25], v[24:25]
	s_nop 0
	v_pk_fma_f32 v[38:39], v[36:37], s[18:19], v[38:39] op_sel_hi:[1,0,0] neg_lo:[1,0,0] neg_hi:[1,0,0]
	s_nop 0
	v_pk_fma_f32 v[38:39], v[36:37], v[38:39], s[28:29] op_sel_hi:[1,1,0]
	s_nop 0
	v_pk_fma_f32 v[38:39], v[36:37], v[38:39], s[30:31] op_sel_hi:[1,1,0]
	s_nop 0
	v_pk_fma_f32 v[38:39], v[36:37], v[38:39], s[34:35] op_sel_hi:[1,1,0]
	s_nop 0
	v_pk_fma_f32 v[38:39], v[36:37], v[38:39], s[36:37] op_sel_hi:[1,1,0]
	s_nop 0
	v_pk_fma_f32 v[38:39], v[36:37], v[38:39], s[38:39] op_sel_hi:[1,1,0]
	s_nop 0
	v_pk_fma_f32 v[36:37], v[36:37], v[38:39], s[40:41] op_sel_hi:[1,1,0]
	s_nop 0
	v_pk_mul_f32 v[24:25], v[24:25], v[36:37]
	s_nop 0
	v_pk_fma_f32 v[26:27], v[26:27], v[24:25], v[26:27]
; __device__ __forceinline__ unsigned cvt_pk_bf16(float lo, float hi) { unsigned r; asm volatile("v_cvt_pk_bf16_f32 %0, %1, %2" : "=v"(r) : "v"(lo), "v"(hi)); return r; }
; __device__ __forceinline__ f32x2 gelu_pk(f32x2 v) {
;     f32x2 x = v * 0.70710678118f;
;     x.x = __builtin_amdgcn_fmed3f(x.x, -2.9f, 2.9f); x.y = __builtin_amdgcn_fmed3f(x.y, -2.9f, 2.9f);
;     const f32x2 t = x * x;
;     f32x2 p = t * (-4.953124630e-07f) + 1.987094038e-05f;
;     p = p * t + (-3.472001117e-04f); p = p * t + 3.517547622e-03f; p = p * t + (-2.333305031e-02f); p = p * t + 1.087993085e-01f; p = p * t + (-3.740358949e-01f); p = p * t + 1.128076553e+00f;
;     const f32x2 hv = v * 0.5f;
;     return hv * (x * p) + hv;
; }
;     __device__ __forceinline__ void operator()(const f32x4 (&acc)[2][2][4][2], const Unit& u, int wr, int wc, int fr, int fq) const {
;     ...
;             for (int m = 0; m < 4; ++m) { bf16_t* rowp = O + (size_t)(row0 + ai * HALF + m * 16) * ldc + col0;
;                 const float rs = rsqrtf(rsv[ai][m] * (1.f / 1024.f) + 1e-6f);
; #pragma unroll
;                 for (int bj = 0; bj < 2; ++bj) if (bj == 0 || !u.q) { f32x4 v0 = acc[ai][bj][m][0] * rs, v1 = acc[ai][bj][m][1] * rs;
;                     if (act) { f32x2 a = gelu_pk((f32x2){v0[0], v0[1]}), b = gelu_pk((f32x2){v0[2], v0[3]}), c = gelu_pk((f32x2){v1[0], v1[1]}), d = gelu_pk((f32x2){v1[2], v1[3]});
;                         v0 = (f32x4){a.x, a.y, b.x, b.y}; v1 = (f32x4){c.x, c.y, d.x, d.y}; }
;                     u32x4 w; w.x = cvt_pk_bf16(v0[0], v0[1]); w.y = cvt_pk_bf16(v0[2], v0[3]); w.z = cvt_pk_bf16(v1[0], v1[1]); w.w = cvt_pk_bf16(v1[2], v1[3]);
;                     *(u32x4*)(rowp + bj * HALF) = w; } }
.LBB0_509:
	v_lshlrev_b64 v[24:25], 10, v[146:147]
	v_mov_b32_e32 v33, v32
	v_lshl_add_u64 v[24:25], s[64:65], 0, v[24:25]
	v_cvt_pk_bf16_f32 v28, v28, v29
	v_cvt_pk_bf16_f32 v29, v30, v31
	v_cvt_pk_bf16_f32 v30, v34, v35
	v_cvt_pk_bf16_f32 v31, v26, v27
	v_mov_b32_e32 v26, v32
	v_mov_b32_e32 v27, v32
	v_lshl_add_u64 v[24:25], v[120:121], 1, v[24:25]
	v_pk_mul_f32 v[22:23], v[22:23], v[26:27]
	v_pk_mul_f32 v[20:21], v[20:21], v[32:33]
	v_pk_mul_f32 v[18:19], v[18:19], v[26:27]
	s_and_b64 vcc, exec, s[10:11]
	v_pk_mul_f32 v[16:17], v[16:17], v[32:33]
	global_store_dwordx4 v[24:25], v[28:31], off sc1
	s_cbranch_vccnz .LBB0_511
	v_pk_mul_f32 v[26:27], v[20:21], s[16:17] op_sel_hi:[1,0]
	v_mov_b64_e32 v[30:31], s[20:21]
	v_med3_f32 v26, v26, s70, v173
	v_med3_f32 v27, v27, s70, v173
	v_pk_mul_f32 v[28:29], v[26:27], v[26:27]
	v_pk_mul_f32 v[20:21], v[20:21], 0.5 op_sel_hi:[1,0]
	v_pk_fma_f32 v[32:33], v[28:29], s[18:19], v[30:31] op_sel_hi:[1,0,0] neg_lo:[1,0,0] neg_hi:[1,0,0]
	s_nop 0
	v_pk_fma_f32 v[32:33], v[28:29], v[32:33], s[28:29] op_sel_hi:[1,1,0]
	s_nop 0
	v_pk_fma_f32 v[32:33], v[28:29], v[32:33], s[30:31] op_sel_hi:[1,1,0]
	s_nop 0
	v_pk_fma_f32 v[32:33], v[28:29], v[32:33], s[34:35] op_sel_hi:[1,1,0]
	s_nop 0
	v_pk_fma_f32 v[32:33], v[28:29], v[32:33], s[36:37] op_sel_hi:[1,1,0]
	s_nop 0
	v_pk_fma_f32 v[32:33], v[28:29], v[32:33], s[38:39] op_sel_hi:[1,1,0]
	s_nop 0
	v_pk_fma_f32 v[28:29], v[28:29], v[32:33], s[40:41] op_sel_hi:[1,1,0]
	s_nop 0
	v_pk_mul_f32 v[26:27], v[26:27], v[28:29]
	s_nop 0
	v_pk_fma_f32 v[20:21], v[20:21], v[26:27], v[20:21]
	v_pk_mul_f32 v[26:27], v[22:23], s[16:17] op_sel_hi:[1,0]
	v_pk_mul_f32 v[22:23], v[22:23], 0.5 op_sel_hi:[1,0]
	v_med3_f32 v26, v26, s70, v173
	v_med3_f32 v27, v27, s70, v173
	v_pk_mul_f32 v[28:29], v[26:27], v[26:27]
	s_nop 0
	v_pk_fma_f32 v[32:33], v[28:29], s[18:19], v[30:31] op_sel_hi:[1,0,0] neg_lo:[1,0,0] neg_hi:[1,0,0]
	s_nop 0
	v_pk_fma_f32 v[32:33], v[28:29], v[32:33], s[28:29] op_sel_hi:[1,1,0]
	s_nop 0
	v_pk_fma_f32 v[32:33], v[28:29], v[32:33], s[30:31] op_sel_hi:[1,1,0]
	s_nop 0
	v_pk_fma_f32 v[32:33], v[28:29], v[32:33], s[34:35] op_sel_hi:[1,1,0]
	s_nop 0
	v_pk_fma_f32 v[32:33], v[28:29], v[32:33], s[36:37] op_sel_hi:[1,1,0]
	s_nop 0
	v_pk_fma_f32 v[32:33], v[28:29], v[32:33], s[38:39] op_sel_hi:[1,1,0]
	s_nop 0
	v_pk_fma_f32 v[28:29], v[28:29], v[32:33], s[40:41] op_sel_hi:[1,1,0]
	s_nop 0
	v_pk_mul_f32 v[26:27], v[26:27], v[28:29]
	s_nop 0
	v_pk_fma_f32 v[22:23], v[22:23], v[26:27], v[22:23]
	v_pk_mul_f32 v[26:27], v[16:17], s[16:17] op_sel_hi:[1,0]
	v_pk_mul_f32 v[16:17], v[16:17], 0.5 op_sel_hi:[1,0]
	v_med3_f32 v26, v26, s70, v173
	v_med3_f32 v27, v27, s70, v173
	v_pk_mul_f32 v[28:29], v[26:27], v[26:27]
	s_nop 0
	v_pk_fma_f32 v[32:33], v[28:29], s[18:19], v[30:31] op_sel_hi:[1,0,0] neg_lo:[1,0,0] neg_hi:[1,0,0]
	s_nop 0
	v_pk_fma_f32 v[32:33], v[28:29], v[32:33], s[28:29] op_sel_hi:[1,1,0]
	s_nop 0
	v_pk_fma_f32 v[32:33], v[28:29], v[32:33], s[30:31] op_sel_hi:[1,1,0]
	s_nop 0
	v_pk_fma_f32 v[32:33], v[28:29], v[32:33], s[34:35] op_sel_hi:[1,1,0]
	s_nop 0
	v_pk_fma_f32 v[32:33], v[28:29], v[32:33], s[36:37] op_sel_hi:[1,1,0]
	s_nop 0
	v_pk_fma_f32 v[32:33], v[28:29], v[32:33], s[38:39] op_sel_hi:[1,1,0]
	s_nop 0
	v_pk_fma_f32 v[28:29], v[28:29], v[32:33], s[40:41] op_sel_hi:[1,1,0]
	s_nop 0
	v_pk_mul_f32 v[26:27], v[26:27], v[28:29]
	s_nop 0
	v_pk_fma_f32 v[16:17], v[16:17], v[26:27], v[16:17]
	v_pk_mul_f32 v[26:27], v[18:19], s[16:17] op_sel_hi:[1,0]
	v_pk_mul_f32 v[18:19], v[18:19], 0.5 op_sel_hi:[1,0]
	v_med3_f32 v26, v26, s70, v173
	v_med3_f32 v27, v27, s70, v173
	v_pk_mul_f32 v[28:29], v[26:27], v[26:27]
	s_nop 0
	v_pk_fma_f32 v[30:31], v[28:29], s[18:19], v[30:31] op_sel_hi:[1,0,0] neg_lo:[1,0,0] neg_hi:[1,0,0]
	s_nop 0
	v_pk_fma_f32 v[30:31], v[28:29], v[30:31], s[28:29] op_sel_hi:[1,1,0]
	s_nop 0
	v_pk_fma_f32 v[30:31], v[28:29], v[30:31], s[30:31] op_sel_hi:[1,1,0]
	s_nop 0
	v_pk_fma_f32 v[30:31], v[28:29], v[30:31], s[34:35] op_sel_hi:[1,1,0]
	s_nop 0
	v_pk_fma_f32 v[30:31], v[28:29], v[30:31], s[36:37] op_sel_hi:[1,1,0]
	s_nop 0
	v_pk_fma_f32 v[30:31], v[28:29], v[30:31], s[38:39] op_sel_hi:[1,1,0]
	s_nop 0
	v_pk_fma_f32 v[28:29], v[28:29], v[30:31], s[40:41] op_sel_hi:[1,1,0]
	s_nop 0
	v_pk_mul_f32 v[26:27], v[26:27], v[28:29]
	s_nop 0
	v_pk_fma_f32 v[18:19], v[18:19], v[26:27], v[18:19]
; __device__ __forceinline__ unsigned cvt_pk_bf16(float lo, float hi) { unsigned r; asm volatile("v_cvt_pk_bf16_f32 %0, %1, %2" : "=v"(r) : "v"(lo), "v"(hi)); return r; }
; __device__ __forceinline__ f32x2 gelu_pk(f32x2 v) {
;     f32x2 x = v * 0.70710678118f;
;     x.x = __builtin_amdgcn_fmed3f(x.x, -2.9f, 2.9f); x.y = __builtin_amdgcn_fmed3f(x.y, -2.9f, 2.9f);
;     const f32x2 t = x * x;
;     f32x2 p = t * (-4.953124630e-07f) + 1.987094038e-05f;
;     p = p * t + (-3.472001117e-04f); p = p * t + 3.517547622e-03f; p = p * t + (-2.333305031e-02f); p = p * t + 1.087993085e-01f; p = p * t + (-3.740358949e-01f); p = p * t + 1.128076553e+00f;
;     const f32x2 hv = v * 0.5f;
;     return hv * (x * p) + hv;
; }
;     __device__ __forceinline__ void operator()(const f32x4 (&acc)[2][2][4][2], const Unit& u, int wr, int wc, int fr, int fq) const {
;     ...
;             for (int m = 0; m < 4; ++m) { bf16_t* rowp = O + (size_t)(row0 + ai * HALF + m * 16) * ldc + col0;
;                 const float rs = rsqrtf(rsv[ai][m] * (1.f / 1024.f) + 1e-6f);
; #pragma unroll
;                 for (int bj = 0; bj < 2; ++bj) if (bj == 0 || !u.q) { f32x4 v0 = acc[ai][bj][m][0] * rs, v1 = acc[ai][bj][m][1] * rs;
;                     if (act) { f32x2 a = gelu_pk((f32x2){v0[0], v0[1]}), b = gelu_pk((f32x2){v0[2], v0[3]}), c = gelu_pk((f32x2){v1[0], v1[1]}), d = gelu_pk((f32x2){v1[2], v1[3]});
;                         v0 = (f32x4){a.x, a.y, b.x, b.y}; v1 = (f32x4){c.x, c.y, d.x, d.y}; }
;                     u32x4 w; w.x = cvt_pk_bf16(v0[0], v0[1]); w.y = cvt_pk_bf16(v0[2], v0[3]); w.z = cvt_pk_bf16(v1[0], v1[1]); w.w = cvt_pk_bf16(v1[2], v1[3]);
;                     *(u32x4*)(rowp + bj * HALF) = w; } }
.LBB0_511:
	v_cvt_pk_bf16_f32 v20, v20, v21
	v_cvt_pk_bf16_f32 v21, v22, v23
	v_fmamk_f32 v22, v174, 0x3a800000, v172
	v_mul_f32_e32 v23, 0x4b800000, v22
	v_cmp_gt_f32_e32 vcc, s63, v22
	s_nop 1
	v_cndmask_b32_e32 v22, v22, v23, vcc
	v_rsq_f32_e32 v26, v22
	v_cvt_pk_bf16_f32 v22, v16, v17
	v_cvt_pk_bf16_f32 v23, v18, v19
	global_store_dwordx4 v[24:25], v[20:23], off offset:256 sc1
	v_mul_f32_e32 v16, 0x45800000, v26
	v_cndmask_b32_e32 v16, v26, v16, vcc
	v_pk_mul_f32 v[14:15], v[14:15], v[16:17] op_sel_hi:[1,0]
	v_pk_mul_f32 v[12:13], v[12:13], v[16:17] op_sel_hi:[1,0]
	v_pk_mul_f32 v[10:11], v[10:11], v[16:17] op_sel_hi:[1,0]
	s_and_b64 vcc, exec, s[10:11]
	v_pk_mul_f32 v[18:19], v[8:9], v[16:17] op_sel_hi:[1,0]
	s_cbranch_vccnz .LBB0_513
	v_pk_mul_f32 v[8:9], v[12:13], s[16:17] op_sel_hi:[1,0]
	v_mov_b64_e32 v[22:23], s[20:21]
	v_med3_f32 v8, v8, s70, v173
	v_med3_f32 v9, v9, s70, v173
	v_pk_mul_f32 v[20:21], v[8:9], v[8:9]
	v_pk_mul_f32 v[12:13], v[12:13], 0.5 op_sel_hi:[1,0]
	v_pk_fma_f32 v[24:25], v[20:21], s[18:19], v[22:23] op_sel_hi:[1,0,0] neg_lo:[1,0,0] neg_hi:[1,0,0]
	s_nop 0
	v_pk_fma_f32 v[24:25], v[20:21], v[24:25], s[28:29] op_sel_hi:[1,1,0]
	s_nop 0
	v_pk_fma_f32 v[24:25], v[20:21], v[24:25], s[30:31] op_sel_hi:[1,1,0]
	s_nop 0
	v_pk_fma_f32 v[24:25], v[20:21], v[24:25], s[34:35] op_sel_hi:[1,1,0]
	s_nop 0
	v_pk_fma_f32 v[24:25], v[20:21], v[24:25], s[36:37] op_sel_hi:[1,1,0]
	s_nop 0
	v_pk_fma_f32 v[24:25], v[20:21], v[24:25], s[38:39] op_sel_hi:[1,1,0]
	s_nop 0
	v_pk_fma_f32 v[20:21], v[20:21], v[24:25], s[40:41] op_sel_hi:[1,1,0]
	s_nop 0
	v_pk_mul_f32 v[8:9], v[8:9], v[20:21]
	s_nop 0
	v_pk_fma_f32 v[12:13], v[12:13], v[8:9], v[12:13]
	v_pk_mul_f32 v[8:9], v[14:15], s[16:17] op_sel_hi:[1,0]
	v_pk_mul_f32 v[14:15], v[14:15], 0.5 op_sel_hi:[1,0]
	v_med3_f32 v8, v8, s70, v173
	v_med3_f32 v9, v9, s70, v173
	v_pk_mul_f32 v[20:21], v[8:9], v[8:9]
	s_nop 0
	v_pk_fma_f32 v[24:25], v[20:21], s[18:19], v[22:23] op_sel_hi:[1,0,0] neg_lo:[1,0,0] neg_hi:[1,0,0]
	s_nop 0
	v_pk_fma_f32 v[24:25], v[20:21], v[24:25], s[28:29] op_sel_hi:[1,1,0]
	s_nop 0
	v_pk_fma_f32 v[24:25], v[20:21], v[24:25], s[30:31] op_sel_hi:[1,1,0]
	s_nop 0
	v_pk_fma_f32 v[24:25], v[20:21], v[24:25], s[34:35] op_sel_hi:[1,1,0]
	s_nop 0
	v_pk_fma_f32 v[24:25], v[20:21], v[24:25], s[36:37] op_sel_hi:[1,1,0]
	s_nop 0
	v_pk_fma_f32 v[24:25], v[20:21], v[24:25], s[38:39] op_sel_hi:[1,1,0]
	s_nop 0
	v_pk_fma_f32 v[20:21], v[20:21], v[24:25], s[40:41] op_sel_hi:[1,1,0]
	s_nop 0
	v_pk_mul_f32 v[8:9], v[8:9], v[20:21]
	s_nop 0
	v_pk_fma_f32 v[14:15], v[14:15], v[8:9], v[14:15]
	v_pk_mul_f32 v[8:9], v[18:19], s[16:17] op_sel_hi:[1,0]
	v_pk_mul_f32 v[18:19], v[18:19], 0.5 op_sel_hi:[1,0]
	v_med3_f32 v8, v8, s70, v173
	v_med3_f32 v9, v9, s70, v173
	v_pk_mul_f32 v[20:21], v[8:9], v[8:9]
	s_nop 0
	v_pk_fma_f32 v[24:25], v[20:21], s[18:19], v[22:23] op_sel_hi:[1,0,0] neg_lo:[1,0,0] neg_hi:[1,0,0]
	s_nop 0
	v_pk_fma_f32 v[24:25], v[20:21], v[24:25], s[28:29] op_sel_hi:[1,1,0]
	s_nop 0
	v_pk_fma_f32 v[24:25], v[20:21], v[24:25], s[30:31] op_sel_hi:[1,1,0]
	s_nop 0
	v_pk_fma_f32 v[24:25], v[20:21], v[24:25], s[34:35] op_sel_hi:[1,1,0]
	s_nop 0
	v_pk_fma_f32 v[24:25], v[20:21], v[24:25], s[36:37] op_sel_hi:[1,1,0]
	s_nop 0
	v_pk_fma_f32 v[24:25], v[20:21], v[24:25], s[38:39] op_sel_hi:[1,1,0]
	s_nop 0
	v_pk_fma_f32 v[20:21], v[20:21], v[24:25], s[40:41] op_sel_hi:[1,1,0]
	s_nop 0
	v_pk_mul_f32 v[8:9], v[8:9], v[20:21]
	s_nop 0
	v_pk_fma_f32 v[18:19], v[18:19], v[8:9], v[18:19]
	v_pk_mul_f32 v[8:9], v[10:11], s[16:17] op_sel_hi:[1,0]
	v_pk_mul_f32 v[10:11], v[10:11], 0.5 op_sel_hi:[1,0]
	v_med3_f32 v8, v8, s70, v173
	v_med3_f32 v9, v9, s70, v173
	v_pk_mul_f32 v[20:21], v[8:9], v[8:9]
	s_nop 0
	v_pk_fma_f32 v[22:23], v[20:21], s[18:19], v[22:23] op_sel_hi:[1,0,0] neg_lo:[1,0,0] neg_hi:[1,0,0]
	s_nop 0
	v_pk_fma_f32 v[22:23], v[20:21], v[22:23], s[28:29] op_sel_hi:[1,1,0]
	s_nop 0
	v_pk_fma_f32 v[22:23], v[20:21], v[22:23], s[30:31] op_sel_hi:[1,1,0]
	s_nop 0
	v_pk_fma_f32 v[22:23], v[20:21], v[22:23], s[34:35] op_sel_hi:[1,1,0]
	s_nop 0
	v_pk_fma_f32 v[22:23], v[20:21], v[22:23], s[36:37] op_sel_hi:[1,1,0]
	s_nop 0
	v_pk_fma_f32 v[22:23], v[20:21], v[22:23], s[38:39] op_sel_hi:[1,1,0]
	s_nop 0
	v_pk_fma_f32 v[20:21], v[20:21], v[22:23], s[40:41] op_sel_hi:[1,1,0]
	s_nop 0
	v_pk_mul_f32 v[8:9], v[8:9], v[20:21]
	s_nop 0
	v_pk_fma_f32 v[10:11], v[10:11], v[8:9], v[10:11]
; __device__ __forceinline__ unsigned cvt_pk_bf16(float lo, float hi) { unsigned r; asm volatile("v_cvt_pk_bf16_f32 %0, %1, %2" : "=v"(r) : "v"(lo), "v"(hi)); return r; }
; #define PG8_BAR __builtin_amdgcn_s_barrier()
;     __device__ __forceinline__ void operator()(const f32x4 (&acc)[2][2][4][2], const Unit& u, int wr, int wc, int fr, int fq) const {
;     ...
;             for (int m = 0; m < 4; ++m) { bf16_t* rowp = O + (size_t)(row0 + ai * HALF + m * 16) * ldc + col0;
;                 const float rs = rsqrtf(rsv[ai][m] * (1.f / 1024.f) + 1e-6f);
; #pragma unroll
;                 for (int bj = 0; bj < 2; ++bj) if (bj == 0 || !u.q) { f32x4 v0 = acc[ai][bj][m][0] * rs, v1 = acc[ai][bj][m][1] * rs;
;                     if (act) { f32x2 a = gelu_pk((f32x2){v0[0], v0[1]}), b = gelu_pk((f32x2){v0[2], v0[3]}), c = gelu_pk((f32x2){v1[0], v1[1]}), d = gelu_pk((f32x2){v1[2], v1[3]});
;                         v0 = (f32x4){a.x, a.y, b.x, b.y}; v1 = (f32x4){c.x, c.y, d.x, d.y}; }
;                     u32x4 w; w.x = cvt_pk_bf16(v0[0], v0[1]); w.y = cvt_pk_bf16(v0[2], v0[3]); w.z = cvt_pk_bf16(v1[0], v1[1]); w.w = cvt_pk_bf16(v1[2], v1[3]);
;                     *(u32x4*)(rowp + bj * HALF) = w; } }
; template <class Epi, class Sched, bool ALIGN_EPI = false, bool SP2 = false>
; __device__ __forceinline__ void gemm_phase(PG8_LAS unsigned char* lds, const Gemm g, const Sched& S, const Epi& E, int wave0) {
;     ...
;         if constexpr (!Epi::AFTER_DRAIN) { E(acc, cur, wr, wc, fr, fq); S.done(cur); }
;         if (!has_next) break;
; #pragma unroll
;         for (int a = 0; a < 2; ++a)
; #pragma unroll
;             for (int b = 0; b < 2; ++b)
; #pragma unroll
;                 for (int m = 0; m < 4; ++m)
; #pragma unroll
;                     for (int n = 0; n < 2; ++n) acc[a][b][m][n] = (f32x4){0.f, 0.f, 0.f, 0.f};
;         cur = nxt; cA = nA; cB = nB; ++ui;
;         if constexpr (ALIGN_EPI) { if (wr == 1) PG8_BAR; }
.LBB0_513:
	v_lshlrev_b64 v[8:9], 10, v[144:145]
	v_mov_b32_e32 v17, v16
	v_lshl_add_u64 v[8:9], s[64:65], 0, v[8:9]
	v_cvt_pk_bf16_f32 v12, v12, v13
	v_cvt_pk_bf16_f32 v13, v14, v15
	v_cvt_pk_bf16_f32 v14, v18, v19
	v_cvt_pk_bf16_f32 v15, v10, v11
	v_mov_b32_e32 v10, v16
	v_mov_b32_e32 v11, v16
	v_lshl_add_u64 v[8:9], v[120:121], 1, v[8:9]
	v_pk_mul_f32 v[6:7], v[6:7], v[10:11]
	v_pk_mul_f32 v[4:5], v[4:5], v[16:17]
	v_pk_mul_f32 v[2:3], v[2:3], v[10:11]
	s_and_b64 vcc, exec, s[10:11]
	v_pk_mul_f32 v[0:1], v[0:1], v[16:17]
	global_store_dwordx4 v[8:9], v[12:15], off sc1
	s_cbranch_vccnz .LBB0_515
	v_pk_mul_f32 v[10:11], v[4:5], s[16:17] op_sel_hi:[1,0]
	v_mov_b64_e32 v[14:15], s[20:21]
	v_med3_f32 v10, v10, s70, v173
	v_med3_f32 v11, v11, s70, v173
	v_pk_mul_f32 v[12:13], v[10:11], v[10:11]
	v_pk_mul_f32 v[4:5], v[4:5], 0.5 op_sel_hi:[1,0]
	v_pk_fma_f32 v[16:17], v[12:13], s[18:19], v[14:15] op_sel_hi:[1,0,0] neg_lo:[1,0,0] neg_hi:[1,0,0]
	s_nop 0
	v_pk_fma_f32 v[16:17], v[12:13], v[16:17], s[28:29] op_sel_hi:[1,1,0]
	s_nop 0
	v_pk_fma_f32 v[16:17], v[12:13], v[16:17], s[30:31] op_sel_hi:[1,1,0]
	s_nop 0
	v_pk_fma_f32 v[16:17], v[12:13], v[16:17], s[34:35] op_sel_hi:[1,1,0]
	s_nop 0
	v_pk_fma_f32 v[16:17], v[12:13], v[16:17], s[36:37] op_sel_hi:[1,1,0]
	s_nop 0
	v_pk_fma_f32 v[16:17], v[12:13], v[16:17], s[38:39] op_sel_hi:[1,1,0]
	s_nop 0
	v_pk_fma_f32 v[12:13], v[12:13], v[16:17], s[40:41] op_sel_hi:[1,1,0]
	s_nop 0
	v_pk_mul_f32 v[10:11], v[10:11], v[12:13]
	s_nop 0
	v_pk_fma_f32 v[4:5], v[4:5], v[10:11], v[4:5]
	v_pk_mul_f32 v[10:11], v[6:7], s[16:17] op_sel_hi:[1,0]
	v_pk_mul_f32 v[6:7], v[6:7], 0.5 op_sel_hi:[1,0]
	v_med3_f32 v10, v10, s70, v173
	v_med3_f32 v11, v11, s70, v173
	v_pk_mul_f32 v[12:13], v[10:11], v[10:11]
	s_nop 0
	v_pk_fma_f32 v[16:17], v[12:13], s[18:19], v[14:15] op_sel_hi:[1,0,0] neg_lo:[1,0,0] neg_hi:[1,0,0]
	s_nop 0
	v_pk_fma_f32 v[16:17], v[12:13], v[16:17], s[28:29] op_sel_hi:[1,1,0]
	s_nop 0
	v_pk_fma_f32 v[16:17], v[12:13], v[16:17], s[30:31] op_sel_hi:[1,1,0]
	s_nop 0
	v_pk_fma_f32 v[16:17], v[12:13], v[16:17], s[34:35] op_sel_hi:[1,1,0]
	s_nop 0
	v_pk_fma_f32 v[16:17], v[12:13], v[16:17], s[36:37] op_sel_hi:[1,1,0]
	s_nop 0
	v_pk_fma_f32 v[16:17], v[12:13], v[16:17], s[38:39] op_sel_hi:[1,1,0]
	s_nop 0
	v_pk_fma_f32 v[12:13], v[12:13], v[16:17], s[40:41] op_sel_hi:[1,1,0]
	s_nop 0
	v_pk_mul_f32 v[10:11], v[10:11], v[12:13]
	s_nop 0
	v_pk_fma_f32 v[6:7], v[6:7], v[10:11], v[6:7]
	v_pk_mul_f32 v[10:11], v[0:1], s[16:17] op_sel_hi:[1,0]
	v_pk_mul_f32 v[0:1], v[0:1], 0.5 op_sel_hi:[1,0]
	v_med3_f32 v10, v10, s70, v173
	v_med3_f32 v11, v11, s70, v173
	v_pk_mul_f32 v[12:13], v[10:11], v[10:11]
	s_nop 0
	v_pk_fma_f32 v[16:17], v[12:13], s[18:19], v[14:15] op_sel_hi:[1,0,0] neg_lo:[1,0,0] neg_hi:[1,0,0]
	s_nop 0
	v_pk_fma_f32 v[16:17], v[12:13], v[16:17], s[28:29] op_sel_hi:[1,1,0]
	s_nop 0
	v_pk_fma_f32 v[16:17], v[12:13], v[16:17], s[30:31] op_sel_hi:[1,1,0]
	s_nop 0
	v_pk_fma_f32 v[16:17], v[12:13], v[16:17], s[34:35] op_sel_hi:[1,1,0]
	s_nop 0
	v_pk_fma_f32 v[16:17], v[12:13], v[16:17], s[36:37] op_sel_hi:[1,1,0]
	s_nop 0
	v_pk_fma_f32 v[16:17], v[12:13], v[16:17], s[38:39] op_sel_hi:[1,1,0]
	s_nop 0
	v_pk_fma_f32 v[12:13], v[12:13], v[16:17], s[40:41] op_sel_hi:[1,1,0]
	s_nop 0
	v_pk_mul_f32 v[10:11], v[10:11], v[12:13]
	s_nop 0
	v_pk_fma_f32 v[0:1], v[0:1], v[10:11], v[0:1]
	v_pk_mul_f32 v[10:11], v[2:3], s[16:17] op_sel_hi:[1,0]
	v_pk_mul_f32 v[2:3], v[2:3], 0.5 op_sel_hi:[1,0]
	v_med3_f32 v10, v10, s70, v173
	v_med3_f32 v11, v11, s70, v173
	v_pk_mul_f32 v[12:13], v[10:11], v[10:11]
	s_nop 0
	v_pk_fma_f32 v[14:15], v[12:13], s[18:19], v[14:15] op_sel_hi:[1,0,0] neg_lo:[1,0,0] neg_hi:[1,0,0]
	s_nop 0
	v_pk_fma_f32 v[14:15], v[12:13], v[14:15], s[28:29] op_sel_hi:[1,1,0]
	s_nop 0
	v_pk_fma_f32 v[14:15], v[12:13], v[14:15], s[30:31] op_sel_hi:[1,1,0]
	s_nop 0
	v_pk_fma_f32 v[14:15], v[12:13], v[14:15], s[34:35] op_sel_hi:[1,1,0]
	s_nop 0
	v_pk_fma_f32 v[14:15], v[12:13], v[14:15], s[36:37] op_sel_hi:[1,1,0]
	s_nop 0
	v_pk_fma_f32 v[14:15], v[12:13], v[14:15], s[38:39] op_sel_hi:[1,1,0]
	s_nop 0
	v_pk_fma_f32 v[12:13], v[12:13], v[14:15], s[40:41] op_sel_hi:[1,1,0]
	s_nop 0
	v_pk_mul_f32 v[10:11], v[10:11], v[12:13]
	s_nop 0
	v_pk_fma_f32 v[2:3], v[2:3], v[10:11], v[2:3]
.LBB0_515:
	s_andn2_b64 vcc, exec, s[8:9]
	s_mov_b64 s[2:3], -1
	v_cvt_pk_bf16_f32 v4, v4, v5
	v_cvt_pk_bf16_f32 v5, v6, v7
	v_cvt_pk_bf16_f32 v6, v0, v1
	v_cvt_pk_bf16_f32 v7, v2, v3
	global_store_dwordx4 v[8:9], v[4:7], off offset:256 sc1
	s_cbranch_vccnz .LBB0_472
	s_andn2_b64 vcc, exec, s[0:1]
	s_cbranch_vccnz .LBB0_471
	s_barrier
	s_branch .LBB0_471

; __device__ __forceinline__ unsigned cvt_pk_bf16(float lo, float hi) { unsigned r; asm volatile("v_cvt_pk_bf16_f32 %0, %1, %2" : "=v"(r) : "v"(lo), "v"(hi)); return r; }
;     __device__ __forceinline__ void operator()(const f32x4 (&acc)[2][2][4][2], const Unit& u, int wr, int wc, int fr, int fq) const {
;     ...
;             for (int m = 0; m < 4; ++m) { bf16_t* rowp = O + (size_t)(row0 + ai * HALF + m * 16) * ldc + col0;
;                 const float rs = rsqrtf(rsv[ai][m] * (1.f / 1024.f) + 1e-6f);
; #pragma unroll
;                 for (int bj = 0; bj < 2; ++bj) if (bj == 0 || !u.q) { f32x4 v0 = acc[ai][bj][m][0] * rs, v1 = acc[ai][bj][m][1] * rs;
;                     if (act) { f32x2 a = gelu_pk((f32x2){v0[0], v0[1]}), b = gelu_pk((f32x2){v0[2], v0[3]}), c = gelu_pk((f32x2){v1[0], v1[1]}), d = gelu_pk((f32x2){v1[2], v1[3]});
;                         v0 = (f32x4){a.x, a.y, b.x, b.y}; v1 = (f32x4){c.x, c.y, d.x, d.y}; }
;                     u32x4 w; w.x = cvt_pk_bf16(v0[0], v0[1]); w.y = cvt_pk_bf16(v0[2], v0[3]); w.z = cvt_pk_bf16(v1[0], v1[1]); w.w = cvt_pk_bf16(v1[2], v1[3]);
;                     *(u32x4*)(rowp + bj * HALF) = w; } }
.LBB0_521:
	v_lshlrev_b64 v[10:11], 10, v[26:27]
	v_lshl_add_u64 v[10:11], s[64:65], 0, v[10:11]
	v_lshl_add_u64 v[10:11], v[30:31], 1, v[10:11]
	v_cvt_pk_bf16_f32 v6, v6, v7
	v_cvt_pk_bf16_f32 v7, v8, v9
	v_cvt_pk_bf16_f32 v8, v2, v3
	v_cvt_pk_bf16_f32 v9, v4, v5
	global_store_dwordx4 v[10:11], v[6:9], off sc1

; __device__ __forceinline__ unsigned cvt_pk_bf16(float lo, float hi) { unsigned r; asm volatile("v_cvt_pk_bf16_f32 %0, %1, %2" : "=v"(r) : "v"(lo), "v"(hi)); return r; }
;     __device__ __forceinline__ void operator()(const f32x4 (&acc)[2][2][4][2], const Unit& u, int wr, int wc, int fr, int fq) const {
;     ...
;             for (int m = 0; m < 4; ++m) { bf16_t* rowp = O + (size_t)(row0 + ai * HALF + m * 16) * ldc + col0;
;                 const float rs = rsqrtf(rsv[ai][m] * (1.f / 1024.f) + 1e-6f);
; #pragma unroll
;                 for (int bj = 0; bj < 2; ++bj) if (bj == 0 || !u.q) { f32x4 v0 = acc[ai][bj][m][0] * rs, v1 = acc[ai][bj][m][1] * rs;
;                     if (act) { f32x2 a = gelu_pk((f32x2){v0[0], v0[1]}), b = gelu_pk((f32x2){v0[2], v0[3]}), c = gelu_pk((f32x2){v1[0], v1[1]}), d = gelu_pk((f32x2){v1[2], v1[3]});
;                         v0 = (f32x4){a.x, a.y, b.x, b.y}; v1 = (f32x4){c.x, c.y, d.x, d.y}; }
;                     u32x4 w; w.x = cvt_pk_bf16(v0[0], v0[1]); w.y = cvt_pk_bf16(v0[2], v0[3]); w.z = cvt_pk_bf16(v1[0], v1[1]); w.w = cvt_pk_bf16(v1[2], v1[3]);
;                     *(u32x4*)(rowp + bj * HALF) = w; } }
.LBB0_536:
	v_cvt_pk_bf16_f32 v46, v42, v43
	v_cvt_pk_bf16_f32 v47, v40, v41
	s_waitcnt vmcnt(2)
	v_fmamk_f32 v40, v45, 0x3a800000, v93
	v_mul_f32_e32 v41, 0x4b800000, v40
	v_cmp_gt_f32_e32 vcc, s7, v40
	s_lshl_b32 s0, s38, 6
	s_or_b32 s0, s0, s6
	v_cndmask_b32_e32 v40, v40, v41, vcc
	v_rsq_f32_e32 v40, v40
	v_lshl_add_u32 v30, v30, 3, s0
	v_lshlrev_b64 v[34:35], 10, v[34:35]
	v_ashrrev_i32_e32 v31, 31, v30
	v_lshl_add_u64 v[34:35], s[64:65], 0, v[34:35]
	v_lshl_add_u64 v[34:35], v[30:31], 1, v[34:35]
	v_cvt_pk_bf16_f32 v48, v38, v39
	v_cvt_pk_bf16_f32 v49, v36, v37
	global_store_dwordx4 v[34:35], v[46:49], off sc1
	v_mul_f32_e32 v34, 0x45800000, v40
	v_cndmask_b32_e32 v34, v40, v34, vcc
	v_pk_mul_f32 v[24:25], v[24:25], v[34:35] op_sel_hi:[1,0]
	v_pk_mul_f32 v[22:23], v[22:23], v[34:35] op_sel_hi:[1,0]
	v_pk_mul_f32 v[20:21], v[20:21], v[34:35] op_sel_hi:[1,0]
	v_cndmask_b32_e64 v35, 0, 1, s[40:41]
	v_cmp_ne_u32_e64 s[0:1], 1, v35
	s_andn2_b64 vcc, exec, s[40:41]
	v_pk_mul_f32 v[18:19], v[18:19], v[34:35] op_sel_hi:[1,0]
	s_cbranch_vccnz .LBB0_538
	v_pk_mul_f32 v[34:35], v[22:23], s[10:11] op_sel_hi:[1,0]
	v_mov_b64_e32 v[38:39], s[16:17]
	v_med3_f32 v34, v34, s11, v94
	v_med3_f32 v35, v35, s11, v94
	v_pk_mul_f32 v[36:37], v[34:35], v[34:35]
	v_pk_mul_f32 v[22:23], v[22:23], 0.5 op_sel_hi:[1,0]
	v_pk_fma_f32 v[40:41], v[36:37], s[14:15], v[38:39] op_sel_hi:[1,0,0] neg_lo:[1,0,0] neg_hi:[1,0,0]
	s_nop 0
	v_pk_fma_f32 v[40:41], v[36:37], v[40:41], s[18:19] op_sel_hi:[1,1,0]
	s_nop 0
	v_pk_fma_f32 v[40:41], v[36:37], v[40:41], s[20:21] op_sel_hi:[1,1,0]
	s_nop 0
	v_pk_fma_f32 v[40:41], v[36:37], v[40:41], s[28:29] op_sel_hi:[1,1,0]
	s_nop 0
	v_pk_fma_f32 v[40:41], v[36:37], v[40:41], s[30:31] op_sel_hi:[1,1,0]
	s_nop 0
	v_pk_fma_f32 v[40:41], v[36:37], v[40:41], s[34:35] op_sel_hi:[1,1,0]
	s_nop 0
	v_pk_fma_f32 v[36:37], v[36:37], v[40:41], s[36:37] op_sel_hi:[1,1,0]
	s_nop 0
	v_pk_mul_f32 v[34:35], v[34:35], v[36:37]
	s_nop 0
	v_pk_fma_f32 v[22:23], v[22:23], v[34:35], v[22:23]
	v_pk_mul_f32 v[34:35], v[24:25], s[10:11] op_sel_hi:[1,0]
	v_pk_mul_f32 v[24:25], v[24:25], 0.5 op_sel_hi:[1,0]
	v_med3_f32 v34, v34, s11, v94
	v_med3_f32 v35, v35, s11, v94
	v_pk_mul_f32 v[36:37], v[34:35], v[34:35]
	s_nop 0
	v_pk_fma_f32 v[40:41], v[36:37], s[14:15], v[38:39] op_sel_hi:[1,0,0] neg_lo:[1,0,0] neg_hi:[1,0,0]
	s_nop 0
	v_pk_fma_f32 v[40:41], v[36:37], v[40:41], s[18:19] op_sel_hi:[1,1,0]
	s_nop 0
	v_pk_fma_f32 v[40:41], v[36:37], v[40:41], s[20:21] op_sel_hi:[1,1,0]
	s_nop 0
	v_pk_fma_f32 v[40:41], v[36:37], v[40:41], s[28:29] op_sel_hi:[1,1,0]
	s_nop 0
	v_pk_fma_f32 v[40:41], v[36:37], v[40:41], s[30:31] op_sel_hi:[1,1,0]
	s_nop 0
	v_pk_fma_f32 v[40:41], v[36:37], v[40:41], s[34:35] op_sel_hi:[1,1,0]
	s_nop 0
	v_pk_fma_f32 v[36:37], v[36:37], v[40:41], s[36:37] op_sel_hi:[1,1,0]
	s_nop 0
	v_pk_mul_f32 v[34:35], v[34:35], v[36:37]
	s_nop 0
	v_pk_fma_f32 v[24:25], v[24:25], v[34:35], v[24:25]
	v_pk_mul_f32 v[34:35], v[18:19], s[10:11] op_sel_hi:[1,0]
	v_pk_mul_f32 v[18:19], v[18:19], 0.5 op_sel_hi:[1,0]
	v_med3_f32 v34, v34, s11, v94
	v_med3_f32 v35, v35, s11, v94
	v_pk_mul_f32 v[36:37], v[34:35], v[34:35]
	s_nop 0
	v_pk_fma_f32 v[40:41], v[36:37], s[14:15], v[38:39] op_sel_hi:[1,0,0] neg_lo:[1,0,0] neg_hi:[1,0,0]
	s_nop 0
	v_pk_fma_f32 v[40:41], v[36:37], v[40:41], s[18:19] op_sel_hi:[1,1,0]
	s_nop 0
	v_pk_fma_f32 v[40:41], v[36:37], v[40:41], s[20:21] op_sel_hi:[1,1,0]
	s_nop 0
	v_pk_fma_f32 v[40:41], v[36:37], v[40:41], s[28:29] op_sel_hi:[1,1,0]
	s_nop 0
	v_pk_fma_f32 v[40:41], v[36:37], v[40:41], s[30:31] op_sel_hi:[1,1,0]
	s_nop 0
	v_pk_fma_f32 v[40:41], v[36:37], v[40:41], s[34:35] op_sel_hi:[1,1,0]
	s_nop 0
	v_pk_fma_f32 v[36:37], v[36:37], v[40:41], s[36:37] op_sel_hi:[1,1,0]
	s_nop 0
	v_pk_mul_f32 v[34:35], v[34:35], v[36:37]
	s_nop 0
	v_pk_fma_f32 v[18:19], v[18:19], v[34:35], v[18:19]
	v_pk_mul_f32 v[34:35], v[20:21], s[10:11] op_sel_hi:[1,0]
	v_pk_mul_f32 v[20:21], v[20:21], 0.5 op_sel_hi:[1,0]
	v_med3_f32 v34, v34, s11, v94
	v_med3_f32 v35, v35, s11, v94
	v_pk_mul_f32 v[36:37], v[34:35], v[34:35]
	s_nop 0
	v_pk_fma_f32 v[38:39], v[36:37], s[14:15], v[38:39] op_sel_hi:[1,0,0] neg_lo:[1,0,0] neg_hi:[1,0,0]
	s_nop 0
	v_pk_fma_f32 v[38:39], v[36:37], v[38:39], s[18:19] op_sel_hi:[1,1,0]
	s_nop 0
	v_pk_fma_f32 v[38:39], v[36:37], v[38:39], s[20:21] op_sel_hi:[1,1,0]
	s_nop 0
	v_pk_fma_f32 v[38:39], v[36:37], v[38:39], s[28:29] op_sel_hi:[1,1,0]
	s_nop 0
	v_pk_fma_f32 v[38:39], v[36:37], v[38:39], s[30:31] op_sel_hi:[1,1,0]
	s_nop 0
	v_pk_fma_f32 v[38:39], v[36:37], v[38:39], s[34:35] op_sel_hi:[1,1,0]
	s_nop 0
	v_pk_fma_f32 v[36:37], v[36:37], v[38:39], s[36:37] op_sel_hi:[1,1,0]
	s_nop 0
	v_pk_mul_f32 v[34:35], v[34:35], v[36:37]
	s_nop 0
	v_pk_fma_f32 v[20:21], v[20:21], v[34:35], v[20:21]
; __device__ __forceinline__ unsigned cvt_pk_bf16(float lo, float hi) { unsigned r; asm volatile("v_cvt_pk_bf16_f32 %0, %1, %2" : "=v"(r) : "v"(lo), "v"(hi)); return r; }
;     __device__ __forceinline__ void operator()(const f32x4 (&acc)[2][2][4][2], const Unit& u, int wr, int wc, int fr, int fq) const {
;     ...
;             for (int m = 0; m < 4; ++m) { bf16_t* rowp = O + (size_t)(row0 + ai * HALF + m * 16) * ldc + col0;
;                 const float rs = rsqrtf(rsv[ai][m] * (1.f / 1024.f) + 1e-6f);
; #pragma unroll
;                 for (int bj = 0; bj < 2; ++bj) if (bj == 0 || !u.q) { f32x4 v0 = acc[ai][bj][m][0] * rs, v1 = acc[ai][bj][m][1] * rs;
;                     if (act) { f32x2 a = gelu_pk((f32x2){v0[0], v0[1]}), b = gelu_pk((f32x2){v0[2], v0[3]}), c = gelu_pk((f32x2){v1[0], v1[1]}), d = gelu_pk((f32x2){v1[2], v1[3]});
;                         v0 = (f32x4){a.x, a.y, b.x, b.y}; v1 = (f32x4){c.x, c.y, d.x, d.y}; }
;                     u32x4 w; w.x = cvt_pk_bf16(v0[0], v0[1]); w.y = cvt_pk_bf16(v0[2], v0[3]); w.z = cvt_pk_bf16(v1[0], v1[1]); w.w = cvt_pk_bf16(v1[2], v1[3]);
;                     *(u32x4*)(rowp + bj * HALF) = w; } }
.LBB0_538:
	v_cvt_pk_bf16_f32 v22, v22, v23
	v_cvt_pk_bf16_f32 v23, v24, v25
	s_waitcnt vmcnt(2)
	v_fmamk_f32 v24, v44, 0x3a800000, v93
	v_mul_f32_e32 v25, 0x4b800000, v24
	v_cmp_gt_f32_e32 vcc, s7, v24
	v_lshlrev_b64 v[32:33], 10, v[32:33]
	v_lshl_add_u64 v[32:33], s[64:65], 0, v[32:33]
	v_cndmask_b32_e32 v24, v24, v25, vcc
	v_rsq_f32_e32 v34, v24
	v_cvt_pk_bf16_f32 v24, v18, v19
	v_lshl_add_u64 v[32:33], v[30:31], 1, v[32:33]
	v_cvt_pk_bf16_f32 v25, v20, v21
	v_mul_f32_e32 v18, 0x45800000, v34
	v_cndmask_b32_e32 v18, v34, v18, vcc
	v_pk_mul_f32 v[16:17], v[16:17], v[18:19] op_sel_hi:[1,0]
	v_pk_mul_f32 v[14:15], v[14:15], v[18:19] op_sel_hi:[1,0]
	v_pk_mul_f32 v[12:13], v[12:13], v[18:19] op_sel_hi:[1,0]
	s_and_b64 vcc, exec, s[0:1]
	v_pk_mul_f32 v[10:11], v[10:11], v[18:19] op_sel_hi:[1,0]
	global_store_dwordx4 v[32:33], v[22:25], off sc1
	s_cbranch_vccnz .LBB0_540
	v_pk_mul_f32 v[18:19], v[14:15], s[10:11] op_sel_hi:[1,0]
	v_mov_b64_e32 v[22:23], s[16:17]
	v_med3_f32 v18, v18, s11, v94
	v_med3_f32 v19, v19, s11, v94
	v_pk_mul_f32 v[20:21], v[18:19], v[18:19]
	v_pk_mul_f32 v[14:15], v[14:15], 0.5 op_sel_hi:[1,0]
	v_pk_fma_f32 v[24:25], v[20:21], s[14:15], v[22:23] op_sel_hi:[1,0,0] neg_lo:[1,0,0] neg_hi:[1,0,0]
	s_nop 0
	v_pk_fma_f32 v[24:25], v[20:21], v[24:25], s[18:19] op_sel_hi:[1,1,0]
	s_nop 0
	v_pk_fma_f32 v[24:25], v[20:21], v[24:25], s[20:21] op_sel_hi:[1,1,0]
	s_nop 0
	v_pk_fma_f32 v[24:25], v[20:21], v[24:25], s[28:29] op_sel_hi:[1,1,0]
	s_nop 0
	v_pk_fma_f32 v[24:25], v[20:21], v[24:25], s[30:31] op_sel_hi:[1,1,0]
	s_nop 0
	v_pk_fma_f32 v[24:25], v[20:21], v[24:25], s[34:35] op_sel_hi:[1,1,0]
	s_nop 0
	v_pk_fma_f32 v[20:21], v[20:21], v[24:25], s[36:37] op_sel_hi:[1,1,0]
	s_nop 0
	v_pk_mul_f32 v[18:19], v[18:19], v[20:21]
	s_nop 0
	v_pk_fma_f32 v[14:15], v[14:15], v[18:19], v[14:15]
	v_pk_mul_f32 v[18:19], v[16:17], s[10:11] op_sel_hi:[1,0]
	v_pk_mul_f32 v[16:17], v[16:17], 0.5 op_sel_hi:[1,0]
	v_med3_f32 v18, v18, s11, v94
	v_med3_f32 v19, v19, s11, v94
	v_pk_mul_f32 v[20:21], v[18:19], v[18:19]
	s_nop 0
	v_pk_fma_f32 v[24:25], v[20:21], s[14:15], v[22:23] op_sel_hi:[1,0,0] neg_lo:[1,0,0] neg_hi:[1,0,0]
	s_nop 0
	v_pk_fma_f32 v[24:25], v[20:21], v[24:25], s[18:19] op_sel_hi:[1,1,0]
	s_nop 0
	v_pk_fma_f32 v[24:25], v[20:21], v[24:25], s[20:21] op_sel_hi:[1,1,0]
	s_nop 0
	v_pk_fma_f32 v[24:25], v[20:21], v[24:25], s[28:29] op_sel_hi:[1,1,0]
	s_nop 0
	v_pk_fma_f32 v[24:25], v[20:21], v[24:25], s[30:31] op_sel_hi:[1,1,0]
	s_nop 0
	v_pk_fma_f32 v[24:25], v[20:21], v[24:25], s[34:35] op_sel_hi:[1,1,0]
	s_nop 0
	v_pk_fma_f32 v[20:21], v[20:21], v[24:25], s[36:37] op_sel_hi:[1,1,0]
	s_nop 0
	v_pk_mul_f32 v[18:19], v[18:19], v[20:21]
	s_nop 0
	v_pk_fma_f32 v[16:17], v[16:17], v[18:19], v[16:17]
	v_pk_mul_f32 v[18:19], v[10:11], s[10:11] op_sel_hi:[1,0]
	v_pk_mul_f32 v[10:11], v[10:11], 0.5 op_sel_hi:[1,0]
	v_med3_f32 v18, v18, s11, v94
	v_med3_f32 v19, v19, s11, v94
	v_pk_mul_f32 v[20:21], v[18:19], v[18:19]
	s_nop 0
	v_pk_fma_f32 v[24:25], v[20:21], s[14:15], v[22:23] op_sel_hi:[1,0,0] neg_lo:[1,0,0] neg_hi:[1,0,0]
	s_nop 0
	v_pk_fma_f32 v[24:25], v[20:21], v[24:25], s[18:19] op_sel_hi:[1,1,0]
	s_nop 0
	v_pk_fma_f32 v[24:25], v[20:21], v[24:25], s[20:21] op_sel_hi:[1,1,0]
	s_nop 0
	v_pk_fma_f32 v[24:25], v[20:21], v[24:25], s[28:29] op_sel_hi:[1,1,0]
	s_nop 0
	v_pk_fma_f32 v[24:25], v[20:21], v[24:25], s[30:31] op_sel_hi:[1,1,0]
	s_nop 0
	v_pk_fma_f32 v[24:25], v[20:21], v[24:25], s[34:35] op_sel_hi:[1,1,0]
	s_nop 0
	v_pk_fma_f32 v[20:21], v[20:21], v[24:25], s[36:37] op_sel_hi:[1,1,0]
	s_nop 0
	v_pk_mul_f32 v[18:19], v[18:19], v[20:21]
	s_nop 0
	v_pk_fma_f32 v[10:11], v[10:11], v[18:19], v[10:11]
	v_pk_mul_f32 v[18:19], v[12:13], s[10:11] op_sel_hi:[1,0]
	v_pk_mul_f32 v[12:13], v[12:13], 0.5 op_sel_hi:[1,0]
	v_med3_f32 v18, v18, s11, v94
	v_med3_f32 v19, v19, s11, v94
	v_pk_mul_f32 v[20:21], v[18:19], v[18:19]
	s_nop 0
	v_pk_fma_f32 v[22:23], v[20:21], s[14:15], v[22:23] op_sel_hi:[1,0,0] neg_lo:[1,0,0] neg_hi:[1,0,0]
	s_nop 0
	v_pk_fma_f32 v[22:23], v[20:21], v[22:23], s[18:19] op_sel_hi:[1,1,0]
	s_nop 0
	v_pk_fma_f32 v[22:23], v[20:21], v[22:23], s[20:21] op_sel_hi:[1,1,0]
	s_nop 0
	v_pk_fma_f32 v[22:23], v[20:21], v[22:23], s[28:29] op_sel_hi:[1,1,0]
	s_nop 0
	v_pk_fma_f32 v[22:23], v[20:21], v[22:23], s[30:31] op_sel_hi:[1,1,0]
	s_nop 0
	v_pk_fma_f32 v[22:23], v[20:21], v[22:23], s[34:35] op_sel_hi:[1,1,0]
	s_nop 0
	v_pk_fma_f32 v[20:21], v[20:21], v[22:23], s[36:37] op_sel_hi:[1,1,0]
	s_nop 0
	v_pk_mul_f32 v[18:19], v[18:19], v[20:21]
	s_nop 0
	v_pk_fma_f32 v[12:13], v[12:13], v[18:19], v[12:13]
; __device__ __forceinline__ unsigned cvt_pk_bf16(float lo, float hi) { unsigned r; asm volatile("v_cvt_pk_bf16_f32 %0, %1, %2" : "=v"(r) : "v"(lo), "v"(hi)); return r; }
;     __device__ __forceinline__ void operator()(const f32x4 (&acc)[2][2][4][2], const Unit& u, int wr, int wc, int fr, int fq) const {
;     ...
;             for (int m = 0; m < 4; ++m) { bf16_t* rowp = O + (size_t)(row0 + ai * HALF + m * 16) * ldc + col0;
;                 const float rs = rsqrtf(rsv[ai][m] * (1.f / 1024.f) + 1e-6f);
; #pragma unroll
;                 for (int bj = 0; bj < 2; ++bj) if (bj == 0 || !u.q) { f32x4 v0 = acc[ai][bj][m][0] * rs, v1 = acc[ai][bj][m][1] * rs;
;                     if (act) { f32x2 a = gelu_pk((f32x2){v0[0], v0[1]}), b = gelu_pk((f32x2){v0[2], v0[3]}), c = gelu_pk((f32x2){v1[0], v1[1]}), d = gelu_pk((f32x2){v1[2], v1[3]});
;                         v0 = (f32x4){a.x, a.y, b.x, b.y}; v1 = (f32x4){c.x, c.y, d.x, d.y}; }
;                     u32x4 w; w.x = cvt_pk_bf16(v0[0], v0[1]); w.y = cvt_pk_bf16(v0[2], v0[3]); w.z = cvt_pk_bf16(v1[0], v1[1]); w.w = cvt_pk_bf16(v1[2], v1[3]);
;                     *(u32x4*)(rowp + bj * HALF) = w; } }
.LBB0_540:
	s_waitcnt vmcnt(2)
	v_fmamk_f32 v1, v1, 0x3a800000, v93
	v_cvt_pk_bf16_f32 v14, v14, v15
	v_cvt_pk_bf16_f32 v15, v16, v17
	v_mul_f32_e32 v16, 0x4b800000, v1
	v_cmp_gt_f32_e32 vcc, s7, v1
	v_lshlrev_b64 v[18:19], 10, v[28:29]
	v_lshl_add_u64 v[18:19], s[64:65], 0, v[18:19]
	v_cndmask_b32_e32 v1, v1, v16, vcc
	v_rsq_f32_e32 v1, v1
	v_cvt_pk_bf16_f32 v16, v10, v11
	v_lshl_add_u64 v[18:19], v[30:31], 1, v[18:19]
	v_cvt_pk_bf16_f32 v17, v12, v13
	v_mul_f32_e32 v10, 0x45800000, v1
	v_cndmask_b32_e32 v10, v1, v10, vcc
	v_pk_mul_f32 v[8:9], v[8:9], v[10:11] op_sel_hi:[1,0]
	v_pk_mul_f32 v[6:7], v[6:7], v[10:11] op_sel_hi:[1,0]
	v_pk_mul_f32 v[4:5], v[4:5], v[10:11] op_sel_hi:[1,0]
	s_and_b64 vcc, exec, s[0:1]
	v_pk_mul_f32 v[2:3], v[2:3], v[10:11] op_sel_hi:[1,0]
	global_store_dwordx4 v[18:19], v[14:17], off sc1
	s_cbranch_vccnz .LBB0_521
	v_pk_mul_f32 v[10:11], v[6:7], s[10:11] op_sel_hi:[1,0]
	v_mov_b64_e32 v[14:15], s[16:17]
	v_med3_f32 v10, v10, s11, v94
	v_med3_f32 v11, v11, s11, v94
	v_pk_mul_f32 v[12:13], v[10:11], v[10:11]
	v_pk_mul_f32 v[6:7], v[6:7], 0.5 op_sel_hi:[1,0]
	v_pk_fma_f32 v[16:17], v[12:13], s[14:15], v[14:15] op_sel_hi:[1,0,0] neg_lo:[1,0,0] neg_hi:[1,0,0]
	s_nop 0
	v_pk_fma_f32 v[16:17], v[12:13], v[16:17], s[18:19] op_sel_hi:[1,1,0]
	s_nop 0
	v_pk_fma_f32 v[16:17], v[12:13], v[16:17], s[20:21] op_sel_hi:[1,1,0]
	s_nop 0
	v_pk_fma_f32 v[16:17], v[12:13], v[16:17], s[28:29] op_sel_hi:[1,1,0]
	s_nop 0
	v_pk_fma_f32 v[16:17], v[12:13], v[16:17], s[30:31] op_sel_hi:[1,1,0]
	s_nop 0
	v_pk_fma_f32 v[16:17], v[12:13], v[16:17], s[34:35] op_sel_hi:[1,1,0]
	s_nop 0
	v_pk_fma_f32 v[12:13], v[12:13], v[16:17], s[36:37] op_sel_hi:[1,1,0]
	s_nop 0
	v_pk_mul_f32 v[10:11], v[10:11], v[12:13]
	s_nop 0
	v_pk_fma_f32 v[6:7], v[6:7], v[10:11], v[6:7]
	v_pk_mul_f32 v[10:11], v[8:9], s[10:11] op_sel_hi:[1,0]
	v_pk_mul_f32 v[8:9], v[8:9], 0.5 op_sel_hi:[1,0]
	v_med3_f32 v10, v10, s11, v94
	v_med3_f32 v11, v11, s11, v94
	v_pk_mul_f32 v[12:13], v[10:11], v[10:11]
	s_nop 0
	v_pk_fma_f32 v[16:17], v[12:13], s[14:15], v[14:15] op_sel_hi:[1,0,0] neg_lo:[1,0,0] neg_hi:[1,0,0]
	s_nop 0
	v_pk_fma_f32 v[16:17], v[12:13], v[16:17], s[18:19] op_sel_hi:[1,1,0]
	s_nop 0
	v_pk_fma_f32 v[16:17], v[12:13], v[16:17], s[20:21] op_sel_hi:[1,1,0]
	s_nop 0
	v_pk_fma_f32 v[16:17], v[12:13], v[16:17], s[28:29] op_sel_hi:[1,1,0]
	s_nop 0
	v_pk_fma_f32 v[16:17], v[12:13], v[16:17], s[30:31] op_sel_hi:[1,1,0]
	s_nop 0
	v_pk_fma_f32 v[16:17], v[12:13], v[16:17], s[34:35] op_sel_hi:[1,1,0]
	s_nop 0
	v_pk_fma_f32 v[12:13], v[12:13], v[16:17], s[36:37] op_sel_hi:[1,1,0]
	s_nop 0
	v_pk_mul_f32 v[10:11], v[10:11], v[12:13]
	s_nop 0
	v_pk_fma_f32 v[8:9], v[8:9], v[10:11], v[8:9]
	v_pk_mul_f32 v[10:11], v[2:3], s[10:11] op_sel_hi:[1,0]
	v_pk_mul_f32 v[2:3], v[2:3], 0.5 op_sel_hi:[1,0]
	v_med3_f32 v10, v10, s11, v94
	v_med3_f32 v11, v11, s11, v94
	v_pk_mul_f32 v[12:13], v[10:11], v[10:11]
	s_nop 0
	v_pk_fma_f32 v[16:17], v[12:13], s[14:15], v[14:15] op_sel_hi:[1,0,0] neg_lo:[1,0,0] neg_hi:[1,0,0]
	s_nop 0
	v_pk_fma_f32 v[16:17], v[12:13], v[16:17], s[18:19] op_sel_hi:[1,1,0]
	s_nop 0
	v_pk_fma_f32 v[16:17], v[12:13], v[16:17], s[20:21] op_sel_hi:[1,1,0]
	s_nop 0
	v_pk_fma_f32 v[16:17], v[12:13], v[16:17], s[28:29] op_sel_hi:[1,1,0]
	s_nop 0
	v_pk_fma_f32 v[16:17], v[12:13], v[16:17], s[30:31] op_sel_hi:[1,1,0]
	s_nop 0
	v_pk_fma_f32 v[16:17], v[12:13], v[16:17], s[34:35] op_sel_hi:[1,1,0]
	s_nop 0
	v_pk_fma_f32 v[12:13], v[12:13], v[16:17], s[36:37] op_sel_hi:[1,1,0]
	s_nop 0
	v_pk_mul_f32 v[10:11], v[10:11], v[12:13]
	s_nop 0
	v_pk_fma_f32 v[2:3], v[2:3], v[10:11], v[2:3]
	v_pk_mul_f32 v[10:11], v[4:5], s[10:11] op_sel_hi:[1,0]
	v_pk_mul_f32 v[4:5], v[4:5], 0.5 op_sel_hi:[1,0]
	v_med3_f32 v10, v10, s11, v94
	v_med3_f32 v11, v11, s11, v94
	v_pk_mul_f32 v[12:13], v[10:11], v[10:11]
	s_nop 0
	v_pk_fma_f32 v[14:15], v[12:13], s[14:15], v[14:15] op_sel_hi:[1,0,0] neg_lo:[1,0,0] neg_hi:[1,0,0]
	s_nop 0
	v_pk_fma_f32 v[14:15], v[12:13], v[14:15], s[18:19] op_sel_hi:[1,1,0]
	s_nop 0
	v_pk_fma_f32 v[14:15], v[12:13], v[14:15], s[20:21] op_sel_hi:[1,1,0]
	s_nop 0
	v_pk_fma_f32 v[14:15], v[12:13], v[14:15], s[28:29] op_sel_hi:[1,1,0]
	s_nop 0
	v_pk_fma_f32 v[14:15], v[12:13], v[14:15], s[30:31] op_sel_hi:[1,1,0]
	s_nop 0
	v_pk_fma_f32 v[14:15], v[12:13], v[14:15], s[34:35] op_sel_hi:[1,1,0]
	s_nop 0
	v_pk_fma_f32 v[12:13], v[12:13], v[14:15], s[36:37] op_sel_hi:[1,1,0]
	s_nop 0
	v_pk_mul_f32 v[10:11], v[10:11], v[12:13]
	s_nop 0
	v_pk_fma_f32 v[4:5], v[4:5], v[10:11], v[4:5]
	s_branch .LBB0_521

; __device__ __forceinline__ unsigned cvt_pk_bf16(float lo, float hi) { unsigned r; asm volatile("v_cvt_pk_bf16_f32 %0, %1, %2" : "=v"(r) : "v"(lo), "v"(hi)); return r; }
;     __device__ __forceinline__ void row_out(const f32x4 v0, const f32x4 v1, int row, int col, float& ss) const {
;         if (C) { float* rowp = C + (size_t)row * ldc + col; __builtin_nontemporal_store(v0, (f32x4*)rowp); __builtin_nontemporal_store(v1, (f32x4*)(rowp + 4)); }
;         if (wxb) { u32x4 w; w.x = cvt_pk_bf16(v0[0], v0[1]); w.y = cvt_pk_bf16(v0[2], v0[3]); w.z = cvt_pk_bf16(v1[0], v1[1]); w.w = cvt_pk_bf16(v1[2], v1[3]);
;             *(u32x4*)(XB0 + (size_t)row * ldc + col) = w;
;             ss += (v0[0] * v0[0] + v0[1] * v0[1]) + (v0[2] * v0[2] + v0[3] * v0[3]) + (v1[0] * v1[0] + v1[1] * v1[1]) + (v1[2] * v1[2] + v1[3] * v1[3]); }
;     __device__ __forceinline__ void operator()(const f32x4 (&acc)[2][2][4][2], const Unit& u, int wr, int wc, int fr, int fq) const {
;     ...
;               for (int mh = 0; mh < 4; mh += 2) {
;                 u32x4 rw[2][2];
; #pragma unroll
;                 for (int mm = 0; mm < 2; ++mm) { const int row = row0 + ai * HALF + (mh + mm) * 16;
; #pragma unroll
;                     for (int bj = 0; bj < 2; ++bj) if (bj == 0 || !u.q) rw[mm][bj] = *(const u32x4*)(XB0 + (size_t)row * ldc + col0 + bj * HALF); }
; #pragma unroll
;                 for (int mm = 0; mm < 2; ++mm) { const int m = mh + mm, row = row0 + ai * HALF + m * 16; float ss = 0.f;
; #pragma unroll
;                     for (int bj = 0; bj < 2; ++bj) if (bj == 0 || !u.q) { const u32x4 w = rw[mm][bj];
;                         const f32x4 v0 = acc[ai][bj][m][0] + (f32x4){bf_lo(w.x), bf_hi(w.x), bf_lo(w.y), bf_hi(w.y)}, v1 = acc[ai][bj][m][1] + (f32x4){bf_lo(w.z), bf_hi(w.z), bf_lo(w.w), bf_hi(w.w)};
;                         row_out(v0, v1, row, col0 + bj * HALF, ss); }
;                     if (wxb) { ss += __shfl_xor(ss, 16); ss += __shfl_xor(ss, 32); if (fq == 0) unsafeAtomicAdd(SS + row, ss); } }
.LBB0_708:
	v_mov_b32_e32 v128, v163
	v_mov_b32_e32 v129, v162
	s_add_i32 s0, s0, s41
	s_nop 0
	v_add_u32_e32 v154, s0, v128
	s_add_i32 s0, s51, s42
	v_lshl_add_u32 v152, v129, 3, s0
	v_ashrrev_i32_e32 v153, 31, v152
	v_lshlrev_b64 v[178:179], 1, v[152:153]
	v_ashrrev_i32_e32 v155, 31, v154
	v_lshl_add_u64 v[156:157], s[96:97], 0, v[178:179]
	v_lshlrev_b64 v[180:181], 11, v[154:155]
	v_cmp_eq_u32_e32 vcc, 0, v129
	v_lshl_add_u64 v[128:129], v[156:157], 0, v[180:181]
	global_load_dwordx4 v[170:173], v[128:129], off
	global_load_dwordx4 v[174:177], v[128:129], off offset:256
	v_add_u32_e32 v158, 16, v154
	v_ashrrev_i32_e32 v159, 31, v158
	v_lshlrev_b64 v[160:161], 11, v[158:159]
	v_lshl_add_u64 v[128:129], v[156:157], 0, v[160:161]
	global_load_dwordx4 v[132:135], v[128:129], off
	s_nop 0
	global_load_dwordx4 v[128:131], v[128:129], off offset:256
	v_lshl_add_u64 v[180:181], s[96:97], 0, v[180:181]
	v_lshl_add_u64 v[178:179], v[180:181], 0, v[178:179]
	s_waitcnt vmcnt(0)
	v_lshlrev_b32_e32 v182, 16, v170
	v_and_b32_e32 v183, 0xffff0000, v170
	v_lshlrev_b32_e32 v170, 16, v171
	v_and_b32_e32 v171, 0xffff0000, v171
	v_pk_add_f32 v[126:127], v[126:127], v[170:171]
	v_lshlrev_b32_e32 v170, 16, v172
	v_and_b32_e32 v171, 0xffff0000, v172
	v_pk_add_f32 v[124:125], v[124:125], v[182:183]
	v_lshlrev_b32_e32 v172, 16, v173
	v_and_b32_e32 v173, 0xffff0000, v173
	v_pk_add_f32 v[170:171], v[120:121], v[170:171]
	v_cvt_pk_bf16_f32 v120, v124, v125
	v_cvt_pk_bf16_f32 v121, v126, v127
	v_pk_add_f32 v[172:173], v[122:123], v[172:173]
	v_cvt_pk_bf16_f32 v122, v170, v171
	s_nop 0
	v_cvt_pk_bf16_f32 v123, v172, v173
	global_store_dwordx4 v[178:179], v[120:123], off sc1
	s_nop 1
	v_mul_f32_e32 v120, v125, v125
	v_mul_f32_e32 v121, v127, v127
	v_fmac_f32_e32 v120, v124, v124
	v_fmac_f32_e32 v121, v126, v126
	v_add_f32_e32 v120, v120, v121
	v_mul_f32_e32 v121, v171, v171
	v_fmac_f32_e32 v121, v170, v170
	v_add_f32_e32 v120, v121, v120
	v_mul_f32_e32 v121, v173, v173
	v_fmac_f32_e32 v121, v172, v172
	v_add_f32_e32 v124, v121, v120
	v_lshlrev_b32_e32 v120, 16, v174
	v_and_b32_e32 v121, 0xffff0000, v174
	v_lshlrev_b32_e32 v122, 16, v175
	v_and_b32_e32 v123, 0xffff0000, v175
	v_pk_add_f32 v[118:119], v[118:119], v[122:123]
	v_pk_add_f32 v[116:117], v[116:117], v[120:121]
	v_lshlrev_b32_e32 v120, 16, v176
	v_and_b32_e32 v121, 0xffff0000, v176
	v_lshlrev_b32_e32 v122, 16, v177
	v_and_b32_e32 v123, 0xffff0000, v177
	v_pk_add_f32 v[122:123], v[114:115], v[122:123]
	v_pk_add_f32 v[120:121], v[112:113], v[120:121]
	v_cvt_pk_bf16_f32 v112, v116, v117
	v_cvt_pk_bf16_f32 v113, v118, v119
	s_nop 0
	v_cvt_pk_bf16_f32 v114, v120, v121
	v_cvt_pk_bf16_f32 v115, v122, v123
	global_store_dwordx4 v[178:179], v[112:115], off offset:256 sc1
	s_nop 1
	v_mul_f32_e32 v114, v117, v117
	v_mul_f32_e32 v115, v119, v119
	v_mul_f32_e32 v113, v121, v121
	v_fmac_f32_e32 v114, v116, v116
	v_fmac_f32_e32 v115, v118, v118
	v_mul_f32_e32 v112, v123, v123
	v_fmac_f32_e32 v113, v120, v120
	v_add_f32_e32 v114, v114, v115
	v_fmac_f32_e32 v112, v122, v122
	v_add_f32_e32 v113, v113, v114
	v_add_f32_e32 v112, v112, v113
	v_and_b32_e32 v114, 64, v168
	v_add_f32_e32 v113, v124, v112
	v_xor_b32_e32 v112, 16, v168
	v_add_u32_e32 v115, 64, v114
	v_cmp_lt_i32_e64 s[0:1], v112, v115
	s_nop 1
	v_cndmask_b32_e64 v112, v168, v112, s[0:1]
	v_lshlrev_b32_e32 v112, 2, v112
	ds_bpermute_b32 v114, v112, v113
	s_waitcnt lgkmcnt(0)
	v_add_f32_e32 v114, v113, v114
	v_xor_b32_e32 v113, 32, v168
	v_cmp_lt_i32_e64 s[0:1], v113, v115
	s_nop 1
	v_cndmask_b32_e64 v113, v168, v113, s[0:1]
	v_lshlrev_b32_e32 v113, 2, v113
	ds_bpermute_b32 v115, v113, v114
	s_and_saveexec_b64 s[0:1], vcc
	s_cbranch_execz .LBB0_710
	s_waitcnt lgkmcnt(0)
	v_add_f32_e32 v116, v114, v115
	v_lshl_add_u64 v[114:115], v[154:155], 2, s[12:13]
	global_atomic_add_f32 v[114:115], v116, off
.LBB0_710:
	s_or_b64 exec, exec, s[0:1]
	v_lshlrev_b32_e32 v114, 16, v132
	s_waitcnt lgkmcnt(0)
	v_and_b32_e32 v115, 0xffff0000, v132
	v_lshlrev_b32_e32 v116, 16, v133
	v_and_b32_e32 v117, 0xffff0000, v133
	v_pk_add_f32 v[108:109], v[108:109], v[114:115]
	v_lshlrev_b32_e32 v114, 16, v134
	v_and_b32_e32 v115, 0xffff0000, v134
	v_pk_add_f32 v[110:111], v[110:111], v[116:117]
	v_pk_add_f32 v[114:115], v[104:105], v[114:115]
	v_cvt_pk_bf16_f32 v104, v108, v109
	v_mul_f32_e32 v109, v109, v109
	v_fmac_f32_e32 v109, v108, v108
	v_mul_f32_e32 v108, v111, v111
	v_fmac_f32_e32 v108, v110, v110
	v_lshlrev_b32_e32 v116, 16, v135
	v_and_b32_e32 v117, 0xffff0000, v135
	v_add_f32_e32 v108, v109, v108
	v_mul_f32_e32 v109, v115, v115
	v_pk_add_f32 v[116:117], v[106:107], v[116:117]
	v_fmac_f32_e32 v109, v114, v114
	v_add_f32_e32 v108, v109, v108
	v_mul_f32_e32 v109, v117, v117
	v_fmac_f32_e32 v109, v116, v116
	v_cvt_pk_bf16_f32 v105, v110, v111
	v_cvt_pk_bf16_f32 v106, v114, v115
	v_add_f32_e32 v114, v109, v108
	v_lshlrev_b32_e32 v108, 16, v128
	v_and_b32_e32 v109, 0xffff0000, v128
	v_lshlrev_b32_e32 v110, 16, v129
	v_and_b32_e32 v111, 0xffff0000, v129
	v_pk_add_f32 v[102:103], v[102:103], v[110:111]
	v_pk_add_f32 v[100:101], v[100:101], v[108:109]
	v_lshlrev_b32_e32 v108, 16, v130
	v_and_b32_e32 v109, 0xffff0000, v130
	v_lshlrev_b32_e32 v110, 16, v131
	v_and_b32_e32 v111, 0xffff0000, v131
	v_pk_add_f32 v[110:111], v[98:99], v[110:111]
	v_pk_add_f32 v[108:109], v[96:97], v[108:109]
	v_mul_f32_e32 v98, v101, v101
	v_mul_f32_e32 v99, v103, v103
	v_mul_f32_e32 v97, v109, v109
	v_fmac_f32_e32 v98, v100, v100
	v_fmac_f32_e32 v99, v102, v102
	v_mul_f32_e32 v96, v111, v111
	v_fmac_f32_e32 v97, v108, v108
	v_add_f32_e32 v98, v98, v99
	v_fmac_f32_e32 v96, v110, v110
	v_add_f32_e32 v97, v97, v98
	v_add_f32_e32 v96, v96, v97
	v_add_f32_e32 v99, v114, v96
	v_cvt_pk_bf16_f32 v107, v116, v117
	ds_bpermute_b32 v116, v112, v99
	v_lshl_add_u64 v[96:97], s[96:97], 0, v[160:161]
	v_lshl_add_u64 v[114:115], v[152:153], 1, v[96:97]
	global_store_dwordx4 v[114:115], v[104:107], off sc1
	v_cvt_pk_bf16_f32 v98, v100, v101
	s_waitcnt lgkmcnt(0)
	v_add_f32_e32 v96, v99, v116
	ds_bpermute_b32 v97, v113, v96
	v_cvt_pk_bf16_f32 v99, v102, v103
	v_cvt_pk_bf16_f32 v100, v108, v109
	v_cvt_pk_bf16_f32 v101, v110, v111
	global_store_dwordx4 v[114:115], v[98:101], off offset:256 sc1
	s_and_saveexec_b64 s[0:1], vcc
	s_cbranch_execz .LBB0_712
	s_waitcnt lgkmcnt(0)
	v_add_f32_e32 v98, v96, v97
	v_lshl_add_u64 v[96:97], v[158:159], 2, s[12:13]
	global_atomic_add_f32 v[96:97], v98, off
; __device__ __forceinline__ unsigned cvt_pk_bf16(float lo, float hi) { unsigned r; asm volatile("v_cvt_pk_bf16_f32 %0, %1, %2" : "=v"(r) : "v"(lo), "v"(hi)); return r; }
;     __device__ __forceinline__ void row_out(const f32x4 v0, const f32x4 v1, int row, int col, float& ss) const {
;         if (C) { float* rowp = C + (size_t)row * ldc + col; __builtin_nontemporal_store(v0, (f32x4*)rowp); __builtin_nontemporal_store(v1, (f32x4*)(rowp + 4)); }
;         if (wxb) { u32x4 w; w.x = cvt_pk_bf16(v0[0], v0[1]); w.y = cvt_pk_bf16(v0[2], v0[3]); w.z = cvt_pk_bf16(v1[0], v1[1]); w.w = cvt_pk_bf16(v1[2], v1[3]);
;             *(u32x4*)(XB0 + (size_t)row * ldc + col) = w;
;             ss += (v0[0] * v0[0] + v0[1] * v0[1]) + (v0[2] * v0[2] + v0[3] * v0[3]) + (v1[0] * v1[0] + v1[1] * v1[1]) + (v1[2] * v1[2] + v1[3] * v1[3]); }
;     __device__ __forceinline__ void operator()(const f32x4 (&acc)[2][2][4][2], const Unit& u, int wr, int wc, int fr, int fq) const {
;     ...
;               for (int mh = 0; mh < 4; mh += 2) {
;                 u32x4 rw[2][2];
; #pragma unroll
;                 for (int mm = 0; mm < 2; ++mm) { const int row = row0 + ai * HALF + (mh + mm) * 16;
; #pragma unroll
;                     for (int bj = 0; bj < 2; ++bj) if (bj == 0 || !u.q) rw[mm][bj] = *(const u32x4*)(XB0 + (size_t)row * ldc + col0 + bj * HALF); }
; #pragma unroll
;                 for (int mm = 0; mm < 2; ++mm) { const int m = mh + mm, row = row0 + ai * HALF + m * 16; float ss = 0.f;
; #pragma unroll
;                     for (int bj = 0; bj < 2; ++bj) if (bj == 0 || !u.q) { const u32x4 w = rw[mm][bj];
;                         const f32x4 v0 = acc[ai][bj][m][0] + (f32x4){bf_lo(w.x), bf_hi(w.x), bf_lo(w.y), bf_hi(w.y)}, v1 = acc[ai][bj][m][1] + (f32x4){bf_lo(w.z), bf_hi(w.z), bf_lo(w.w), bf_hi(w.w)};
;                         row_out(v0, v1, row, col0 + bj * HALF, ss); }
;                     if (wxb) { ss += __shfl_xor(ss, 16); ss += __shfl_xor(ss, 32); if (fq == 0) unsafeAtomicAdd(SS + row, ss); } }
.LBB0_712:
	s_or_b64 exec, exec, s[0:1]
	v_add_u32_e32 v108, 32, v154
	v_ashrrev_i32_e32 v109, 31, v108
	v_lshlrev_b64 v[110:111], 11, v[108:109]
	s_waitcnt lgkmcnt(0)
	v_lshl_add_u64 v[96:97], v[156:157], 0, v[110:111]
	global_load_dwordx4 v[114:117], v[96:97], off
	global_load_dwordx4 v[118:121], v[96:97], off offset:256
	v_add_u32_e32 v104, 48, v154
	v_ashrrev_i32_e32 v105, 31, v104
	v_lshlrev_b64 v[106:107], 11, v[104:105]
	v_lshl_add_u64 v[96:97], v[156:157], 0, v[106:107]
	global_load_dwordx4 v[100:103], v[96:97], off
	s_nop 0
	global_load_dwordx4 v[96:99], v[96:97], off offset:256
	v_lshl_add_u64 v[110:111], s[96:97], 0, v[110:111]
	v_lshl_add_u64 v[110:111], v[152:153], 1, v[110:111]
	s_waitcnt vmcnt(3)
	v_lshlrev_b32_e32 v122, 16, v114
	v_and_b32_e32 v123, 0xffff0000, v114
	v_lshlrev_b32_e32 v114, 16, v115
	v_and_b32_e32 v115, 0xffff0000, v115
	v_pk_add_f32 v[94:95], v[94:95], v[114:115]
	v_lshlrev_b32_e32 v114, 16, v116
	v_and_b32_e32 v115, 0xffff0000, v116
	v_pk_add_f32 v[92:93], v[92:93], v[122:123]
	v_lshlrev_b32_e32 v116, 16, v117
	v_and_b32_e32 v117, 0xffff0000, v117
	v_pk_add_f32 v[114:115], v[88:89], v[114:115]
	v_cvt_pk_bf16_f32 v88, v92, v93
	v_cvt_pk_bf16_f32 v89, v94, v95
	v_pk_add_f32 v[116:117], v[90:91], v[116:117]
	v_cvt_pk_bf16_f32 v90, v114, v115
	s_nop 0
	v_cvt_pk_bf16_f32 v91, v116, v117
	global_store_dwordx4 v[110:111], v[88:91], off sc1
	s_nop 1
	v_mul_f32_e32 v88, v93, v93
	v_mul_f32_e32 v89, v95, v95
	v_fmac_f32_e32 v88, v92, v92
	v_fmac_f32_e32 v89, v94, v94
	v_add_f32_e32 v88, v88, v89
	v_mul_f32_e32 v89, v115, v115
	v_fmac_f32_e32 v89, v114, v114
	v_add_f32_e32 v88, v89, v88
	v_mul_f32_e32 v89, v117, v117
	v_fmac_f32_e32 v89, v116, v116
	v_add_f32_e32 v92, v89, v88
	s_waitcnt vmcnt(3)
	v_lshlrev_b32_e32 v88, 16, v118
	v_and_b32_e32 v89, 0xffff0000, v118
	v_lshlrev_b32_e32 v90, 16, v119
	v_and_b32_e32 v91, 0xffff0000, v119
	v_pk_add_f32 v[86:87], v[86:87], v[90:91]
	v_pk_add_f32 v[84:85], v[84:85], v[88:89]
	v_lshlrev_b32_e32 v88, 16, v120
	v_and_b32_e32 v89, 0xffff0000, v120
	v_lshlrev_b32_e32 v90, 16, v121
	v_and_b32_e32 v91, 0xffff0000, v121
	v_pk_add_f32 v[90:91], v[82:83], v[90:91]
	v_pk_add_f32 v[88:89], v[80:81], v[88:89]
	v_cvt_pk_bf16_f32 v80, v84, v85
	v_cvt_pk_bf16_f32 v81, v86, v87
	s_nop 0
	v_cvt_pk_bf16_f32 v82, v88, v89
	v_cvt_pk_bf16_f32 v83, v90, v91
	global_store_dwordx4 v[110:111], v[80:83], off offset:256 sc1
	s_nop 1
	v_mul_f32_e32 v82, v85, v85
	v_mul_f32_e32 v83, v87, v87
	v_mul_f32_e32 v81, v89, v89
	v_fmac_f32_e32 v82, v84, v84
	v_fmac_f32_e32 v83, v86, v86
	v_mul_f32_e32 v80, v91, v91
	v_fmac_f32_e32 v81, v88, v88
	v_add_f32_e32 v82, v82, v83
	v_fmac_f32_e32 v80, v90, v90
	v_add_f32_e32 v81, v81, v82
	v_add_f32_e32 v80, v80, v81
	v_add_f32_e32 v80, v92, v80
	ds_bpermute_b32 v81, v112, v80
	s_waitcnt lgkmcnt(0)
	v_add_f32_e32 v80, v80, v81
	ds_bpermute_b32 v81, v113, v80
	s_and_saveexec_b64 s[0:1], vcc
	s_cbranch_execz .LBB0_714
	s_waitcnt lgkmcnt(0)
	v_add_f32_e32 v82, v80, v81
	v_lshl_add_u64 v[80:81], v[108:109], 2, s[12:13]
	global_atomic_add_f32 v[80:81], v82, off
.LBB0_714:
	s_or_b64 exec, exec, s[0:1]
	s_waitcnt vmcnt(3)
	v_lshlrev_b32_e32 v80, 16, v100
	s_waitcnt lgkmcnt(0)
	v_and_b32_e32 v81, 0xffff0000, v100
	v_lshlrev_b32_e32 v82, 16, v101
	v_and_b32_e32 v83, 0xffff0000, v101
	v_pk_add_f32 v[76:77], v[76:77], v[80:81]
	v_lshlrev_b32_e32 v80, 16, v102
	v_and_b32_e32 v81, 0xffff0000, v102
	v_pk_add_f32 v[78:79], v[78:79], v[82:83]
	v_pk_add_f32 v[80:81], v[72:73], v[80:81]
	v_cvt_pk_bf16_f32 v72, v76, v77
	v_mul_f32_e32 v77, v77, v77
	v_fmac_f32_e32 v77, v76, v76
	v_mul_f32_e32 v76, v79, v79
	v_fmac_f32_e32 v76, v78, v78
	v_lshlrev_b32_e32 v82, 16, v103
	v_and_b32_e32 v83, 0xffff0000, v103
	v_add_f32_e32 v76, v77, v76
	v_mul_f32_e32 v77, v81, v81
	v_pk_add_f32 v[82:83], v[74:75], v[82:83]
	v_fmac_f32_e32 v77, v80, v80
	v_add_f32_e32 v76, v77, v76
	v_mul_f32_e32 v77, v83, v83
	v_fmac_f32_e32 v77, v82, v82
	v_cvt_pk_bf16_f32 v73, v78, v79
	v_cvt_pk_bf16_f32 v74, v80, v81
	v_add_f32_e32 v80, v77, v76
	s_waitcnt vmcnt(2)
	v_lshlrev_b32_e32 v76, 16, v96
	v_and_b32_e32 v77, 0xffff0000, v96
	v_lshlrev_b32_e32 v78, 16, v97
	v_and_b32_e32 v79, 0xffff0000, v97
	v_pk_add_f32 v[70:71], v[70:71], v[78:79]
	v_pk_add_f32 v[68:69], v[68:69], v[76:77]
	v_lshlrev_b32_e32 v76, 16, v98
	v_and_b32_e32 v77, 0xffff0000, v98
	v_lshlrev_b32_e32 v78, 16, v99
	v_and_b32_e32 v79, 0xffff0000, v99
	v_pk_add_f32 v[78:79], v[66:67], v[78:79]
	v_pk_add_f32 v[76:77], v[64:65], v[76:77]
	v_mul_f32_e32 v66, v69, v69
	v_mul_f32_e32 v67, v71, v71
	v_mul_f32_e32 v65, v77, v77
	v_fmac_f32_e32 v66, v68, v68
	v_fmac_f32_e32 v67, v70, v70
	v_mul_f32_e32 v64, v79, v79
	v_fmac_f32_e32 v65, v76, v76
	v_add_f32_e32 v66, v66, v67
	v_fmac_f32_e32 v64, v78, v78
	v_add_f32_e32 v65, v65, v66
	v_add_f32_e32 v64, v64, v65
	v_add_f32_e32 v67, v80, v64
	v_cvt_pk_bf16_f32 v75, v82, v83
	ds_bpermute_b32 v82, v112, v67
	v_lshl_add_u64 v[64:65], s[96:97], 0, v[106:107]
	v_lshl_add_u64 v[80:81], v[152:153], 1, v[64:65]
	global_store_dwordx4 v[80:81], v[72:75], off sc1
	v_cvt_pk_bf16_f32 v66, v68, v69
	s_waitcnt lgkmcnt(0)
	v_add_f32_e32 v64, v67, v82
	ds_bpermute_b32 v65, v113, v64
	v_cvt_pk_bf16_f32 v67, v70, v71
	v_cvt_pk_bf16_f32 v68, v76, v77
	v_cvt_pk_bf16_f32 v69, v78, v79
	global_store_dwordx4 v[80:81], v[66:69], off offset:256 sc1
	s_and_saveexec_b64 s[0:1], vcc
	s_cbranch_execz .LBB0_716
	s_waitcnt lgkmcnt(0)
	v_add_f32_e32 v66, v64, v65
	v_lshl_add_u64 v[64:65], v[104:105], 2, s[12:13]
	global_atomic_add_f32 v[64:65], v66, off
; __device__ __forceinline__ unsigned cvt_pk_bf16(float lo, float hi) { unsigned r; asm volatile("v_cvt_pk_bf16_f32 %0, %1, %2" : "=v"(r) : "v"(lo), "v"(hi)); return r; }
;     __device__ __forceinline__ void row_out(const f32x4 v0, const f32x4 v1, int row, int col, float& ss) const {
;         if (C) { float* rowp = C + (size_t)row * ldc + col; __builtin_nontemporal_store(v0, (f32x4*)rowp); __builtin_nontemporal_store(v1, (f32x4*)(rowp + 4)); }
;         if (wxb) { u32x4 w; w.x = cvt_pk_bf16(v0[0], v0[1]); w.y = cvt_pk_bf16(v0[2], v0[3]); w.z = cvt_pk_bf16(v1[0], v1[1]); w.w = cvt_pk_bf16(v1[2], v1[3]);
;             *(u32x4*)(XB0 + (size_t)row * ldc + col) = w;
;             ss += (v0[0] * v0[0] + v0[1] * v0[1]) + (v0[2] * v0[2] + v0[3] * v0[3]) + (v1[0] * v1[0] + v1[1] * v1[1]) + (v1[2] * v1[2] + v1[3] * v1[3]); }
;     __device__ __forceinline__ void operator()(const f32x4 (&acc)[2][2][4][2], const Unit& u, int wr, int wc, int fr, int fq) const {
;     ...
;               for (int mh = 0; mh < 4; mh += 2) {
;                 u32x4 rw[2][2];
; #pragma unroll
;                 for (int mm = 0; mm < 2; ++mm) { const int row = row0 + ai * HALF + (mh + mm) * 16;
; #pragma unroll
;                     for (int bj = 0; bj < 2; ++bj) if (bj == 0 || !u.q) rw[mm][bj] = *(const u32x4*)(XB0 + (size_t)row * ldc + col0 + bj * HALF); }
; #pragma unroll
;                 for (int mm = 0; mm < 2; ++mm) { const int m = mh + mm, row = row0 + ai * HALF + m * 16; float ss = 0.f;
; #pragma unroll
;                     for (int bj = 0; bj < 2; ++bj) if (bj == 0 || !u.q) { const u32x4 w = rw[mm][bj];
;                         const f32x4 v0 = acc[ai][bj][m][0] + (f32x4){bf_lo(w.x), bf_hi(w.x), bf_lo(w.y), bf_hi(w.y)}, v1 = acc[ai][bj][m][1] + (f32x4){bf_lo(w.z), bf_hi(w.z), bf_lo(w.w), bf_hi(w.w)};
;                         row_out(v0, v1, row, col0 + bj * HALF, ss); }
;                     if (wxb) { ss += __shfl_xor(ss, 16); ss += __shfl_xor(ss, 32); if (fq == 0) unsafeAtomicAdd(SS + row, ss); } }
.LBB0_716:
	s_or_b64 exec, exec, s[0:1]
	v_add_u32_e32 v76, 0x80, v154
	v_ashrrev_i32_e32 v77, 31, v76
	v_lshlrev_b64 v[86:87], 11, v[76:77]
	s_waitcnt lgkmcnt(0)
	v_lshl_add_u64 v[64:65], v[156:157], 0, v[86:87]
	global_load_dwordx4 v[78:81], v[64:65], off
	global_load_dwordx4 v[82:85], v[64:65], off offset:256
	v_add_u32_e32 v72, 0x90, v154
	v_ashrrev_i32_e32 v73, 31, v72
	v_lshlrev_b64 v[74:75], 11, v[72:73]
	v_lshl_add_u64 v[64:65], v[156:157], 0, v[74:75]
	global_load_dwordx4 v[68:71], v[64:65], off
	s_nop 0
	global_load_dwordx4 v[64:67], v[64:65], off offset:256
	v_lshl_add_u64 v[86:87], s[96:97], 0, v[86:87]
	v_lshl_add_u64 v[86:87], v[152:153], 1, v[86:87]
	s_waitcnt vmcnt(3)
	v_lshlrev_b32_e32 v88, 16, v78
	v_and_b32_e32 v89, 0xffff0000, v78
	v_lshlrev_b32_e32 v78, 16, v79
	v_and_b32_e32 v79, 0xffff0000, v79
	v_pk_add_f32 v[62:63], v[62:63], v[78:79]
	v_lshlrev_b32_e32 v78, 16, v80
	v_and_b32_e32 v79, 0xffff0000, v80
	v_pk_add_f32 v[60:61], v[60:61], v[88:89]
	v_lshlrev_b32_e32 v80, 16, v81
	v_and_b32_e32 v81, 0xffff0000, v81
	v_pk_add_f32 v[78:79], v[56:57], v[78:79]
	v_cvt_pk_bf16_f32 v56, v60, v61
	v_cvt_pk_bf16_f32 v57, v62, v63
	v_pk_add_f32 v[80:81], v[58:59], v[80:81]
	v_cvt_pk_bf16_f32 v58, v78, v79
	s_nop 0
	v_cvt_pk_bf16_f32 v59, v80, v81
	global_store_dwordx4 v[86:87], v[56:59], off sc1
	s_nop 1
	v_mul_f32_e32 v56, v61, v61
	v_mul_f32_e32 v57, v63, v63
	v_fmac_f32_e32 v56, v60, v60
	v_fmac_f32_e32 v57, v62, v62
	v_add_f32_e32 v56, v56, v57
	v_mul_f32_e32 v57, v79, v79
	v_fmac_f32_e32 v57, v78, v78
	v_add_f32_e32 v56, v57, v56
	v_mul_f32_e32 v57, v81, v81
	v_fmac_f32_e32 v57, v80, v80
	v_add_f32_e32 v60, v57, v56
	s_waitcnt vmcnt(3)
	v_lshlrev_b32_e32 v56, 16, v82
	v_and_b32_e32 v57, 0xffff0000, v82
	v_lshlrev_b32_e32 v58, 16, v83
	v_and_b32_e32 v59, 0xffff0000, v83
	v_pk_add_f32 v[54:55], v[54:55], v[58:59]
	v_pk_add_f32 v[52:53], v[52:53], v[56:57]
	v_lshlrev_b32_e32 v56, 16, v84
	v_and_b32_e32 v57, 0xffff0000, v84
	v_lshlrev_b32_e32 v58, 16, v85
	v_and_b32_e32 v59, 0xffff0000, v85
	v_pk_add_f32 v[58:59], v[50:51], v[58:59]
	v_pk_add_f32 v[56:57], v[48:49], v[56:57]
	v_cvt_pk_bf16_f32 v48, v52, v53
	v_cvt_pk_bf16_f32 v49, v54, v55
	s_nop 0
	v_cvt_pk_bf16_f32 v50, v56, v57
	v_cvt_pk_bf16_f32 v51, v58, v59
	global_store_dwordx4 v[86:87], v[48:51], off offset:256 sc1
	s_nop 1
	v_mul_f32_e32 v50, v53, v53
	v_mul_f32_e32 v51, v55, v55
	v_mul_f32_e32 v49, v57, v57
	v_fmac_f32_e32 v50, v52, v52
	v_fmac_f32_e32 v51, v54, v54
	v_mul_f32_e32 v48, v59, v59
	v_fmac_f32_e32 v49, v56, v56
	v_add_f32_e32 v50, v50, v51
	v_fmac_f32_e32 v48, v58, v58
	v_add_f32_e32 v49, v49, v50
	v_add_f32_e32 v48, v48, v49
	v_add_f32_e32 v48, v60, v48
	ds_bpermute_b32 v49, v112, v48
	s_waitcnt lgkmcnt(0)
	v_add_f32_e32 v48, v48, v49
	ds_bpermute_b32 v49, v113, v48
	s_and_saveexec_b64 s[0:1], vcc
	s_cbranch_execz .LBB0_718
	s_waitcnt lgkmcnt(0)
	v_add_f32_e32 v50, v48, v49
	v_lshl_add_u64 v[48:49], v[76:77], 2, s[12:13]
	global_atomic_add_f32 v[48:49], v50, off
.LBB0_718:
	s_or_b64 exec, exec, s[0:1]
	s_waitcnt vmcnt(3)
	v_lshlrev_b32_e32 v48, 16, v68
	s_waitcnt lgkmcnt(0)
	v_and_b32_e32 v49, 0xffff0000, v68
	v_lshlrev_b32_e32 v50, 16, v69
	v_and_b32_e32 v51, 0xffff0000, v69
	v_pk_add_f32 v[44:45], v[44:45], v[48:49]
	v_lshlrev_b32_e32 v48, 16, v70
	v_and_b32_e32 v49, 0xffff0000, v70
	v_pk_add_f32 v[46:47], v[46:47], v[50:51]
	v_pk_add_f32 v[48:49], v[40:41], v[48:49]
	v_cvt_pk_bf16_f32 v40, v44, v45
	v_mul_f32_e32 v45, v45, v45
	v_fmac_f32_e32 v45, v44, v44
	v_mul_f32_e32 v44, v47, v47
	v_fmac_f32_e32 v44, v46, v46
	v_lshlrev_b32_e32 v50, 16, v71
	v_and_b32_e32 v51, 0xffff0000, v71
	v_add_f32_e32 v44, v45, v44
	v_mul_f32_e32 v45, v49, v49
	v_pk_add_f32 v[50:51], v[42:43], v[50:51]
	v_fmac_f32_e32 v45, v48, v48
	v_add_f32_e32 v44, v45, v44
	v_mul_f32_e32 v45, v51, v51
	v_fmac_f32_e32 v45, v50, v50
	v_cvt_pk_bf16_f32 v41, v46, v47
	v_cvt_pk_bf16_f32 v42, v48, v49
	v_add_f32_e32 v48, v45, v44
	s_waitcnt vmcnt(2)
	v_lshlrev_b32_e32 v44, 16, v64
	v_and_b32_e32 v45, 0xffff0000, v64
	v_lshlrev_b32_e32 v46, 16, v65
	v_and_b32_e32 v47, 0xffff0000, v65
	v_pk_add_f32 v[38:39], v[38:39], v[46:47]
	v_pk_add_f32 v[36:37], v[36:37], v[44:45]
	v_lshlrev_b32_e32 v44, 16, v66
	v_and_b32_e32 v45, 0xffff0000, v66
	v_lshlrev_b32_e32 v46, 16, v67
	v_and_b32_e32 v47, 0xffff0000, v67
	v_pk_add_f32 v[46:47], v[34:35], v[46:47]
	v_pk_add_f32 v[44:45], v[32:33], v[44:45]
	v_mul_f32_e32 v34, v37, v37
	v_mul_f32_e32 v35, v39, v39
	v_mul_f32_e32 v33, v45, v45
	v_fmac_f32_e32 v34, v36, v36
	v_fmac_f32_e32 v35, v38, v38
	v_mul_f32_e32 v32, v47, v47
	v_fmac_f32_e32 v33, v44, v44
	v_add_f32_e32 v34, v34, v35
	v_fmac_f32_e32 v32, v46, v46
	v_add_f32_e32 v33, v33, v34
	v_add_f32_e32 v32, v32, v33
	v_add_f32_e32 v35, v48, v32
	v_cvt_pk_bf16_f32 v43, v50, v51
	ds_bpermute_b32 v50, v112, v35
	v_lshl_add_u64 v[32:33], s[96:97], 0, v[74:75]
	v_lshl_add_u64 v[48:49], v[152:153], 1, v[32:33]
	global_store_dwordx4 v[48:49], v[40:43], off sc1
	v_cvt_pk_bf16_f32 v34, v36, v37
	s_waitcnt lgkmcnt(0)
	v_add_f32_e32 v32, v35, v50
	ds_bpermute_b32 v33, v113, v32
	v_cvt_pk_bf16_f32 v35, v38, v39
	v_cvt_pk_bf16_f32 v36, v44, v45
	v_cvt_pk_bf16_f32 v37, v46, v47
	global_store_dwordx4 v[48:49], v[34:37], off offset:256 sc1
	s_and_saveexec_b64 s[0:1], vcc
	s_cbranch_execz .LBB0_720
	s_waitcnt lgkmcnt(0)
	v_add_f32_e32 v34, v32, v33
	v_lshl_add_u64 v[32:33], v[72:73], 2, s[12:13]
	global_atomic_add_f32 v[32:33], v34, off
; __device__ __forceinline__ unsigned cvt_pk_bf16(float lo, float hi) { unsigned r; asm volatile("v_cvt_pk_bf16_f32 %0, %1, %2" : "=v"(r) : "v"(lo), "v"(hi)); return r; }
;     __device__ __forceinline__ void row_out(const f32x4 v0, const f32x4 v1, int row, int col, float& ss) const {
;         if (C) { float* rowp = C + (size_t)row * ldc + col; __builtin_nontemporal_store(v0, (f32x4*)rowp); __builtin_nontemporal_store(v1, (f32x4*)(rowp + 4)); }
;         if (wxb) { u32x4 w; w.x = cvt_pk_bf16(v0[0], v0[1]); w.y = cvt_pk_bf16(v0[2], v0[3]); w.z = cvt_pk_bf16(v1[0], v1[1]); w.w = cvt_pk_bf16(v1[2], v1[3]);
;             *(u32x4*)(XB0 + (size_t)row * ldc + col) = w;
;             ss += (v0[0] * v0[0] + v0[1] * v0[1]) + (v0[2] * v0[2] + v0[3] * v0[3]) + (v1[0] * v1[0] + v1[1] * v1[1]) + (v1[2] * v1[2] + v1[3] * v1[3]); }
;     __device__ __forceinline__ void operator()(const f32x4 (&acc)[2][2][4][2], const Unit& u, int wr, int wc, int fr, int fq) const {
;     ...
;               for (int mh = 0; mh < 4; mh += 2) {
;                 u32x4 rw[2][2];
; #pragma unroll
;                 for (int mm = 0; mm < 2; ++mm) { const int row = row0 + ai * HALF + (mh + mm) * 16;
; #pragma unroll
;                     for (int bj = 0; bj < 2; ++bj) if (bj == 0 || !u.q) rw[mm][bj] = *(const u32x4*)(XB0 + (size_t)row * ldc + col0 + bj * HALF); }
; #pragma unroll
;                 for (int mm = 0; mm < 2; ++mm) { const int m = mh + mm, row = row0 + ai * HALF + m * 16; float ss = 0.f;
; #pragma unroll
;                     for (int bj = 0; bj < 2; ++bj) if (bj == 0 || !u.q) { const u32x4 w = rw[mm][bj];
;                         const f32x4 v0 = acc[ai][bj][m][0] + (f32x4){bf_lo(w.x), bf_hi(w.x), bf_lo(w.y), bf_hi(w.y)}, v1 = acc[ai][bj][m][1] + (f32x4){bf_lo(w.z), bf_hi(w.z), bf_lo(w.w), bf_hi(w.w)};
;                         row_out(v0, v1, row, col0 + bj * HALF, ss); }
;                     if (wxb) { ss += __shfl_xor(ss, 16); ss += __shfl_xor(ss, 32); if (fq == 0) unsafeAtomicAdd(SS + row, ss); } }
.LBB0_720:
	s_or_b64 exec, exec, s[0:1]
	v_add_u32_e32 v44, 0xa0, v154
	v_ashrrev_i32_e32 v45, 31, v44
	v_lshlrev_b64 v[54:55], 11, v[44:45]
	s_waitcnt lgkmcnt(0)
	v_lshl_add_u64 v[32:33], v[156:157], 0, v[54:55]
	global_load_dwordx4 v[46:49], v[32:33], off
	global_load_dwordx4 v[50:53], v[32:33], off offset:256
	v_add_u32_e32 v40, 0xb0, v154
	v_ashrrev_i32_e32 v41, 31, v40
	v_lshlrev_b64 v[42:43], 11, v[40:41]
	v_lshl_add_u64 v[32:33], v[156:157], 0, v[42:43]
	global_load_dwordx4 v[36:39], v[32:33], off
	s_nop 0
	global_load_dwordx4 v[32:35], v[32:33], off offset:256
	v_lshl_add_u64 v[54:55], s[96:97], 0, v[54:55]
	v_lshl_add_u64 v[54:55], v[152:153], 1, v[54:55]
	s_waitcnt vmcnt(3)
	v_lshlrev_b32_e32 v56, 16, v46
	v_and_b32_e32 v57, 0xffff0000, v46
	v_lshlrev_b32_e32 v46, 16, v47
	v_and_b32_e32 v47, 0xffff0000, v47
	v_pk_add_f32 v[30:31], v[30:31], v[46:47]
	v_lshlrev_b32_e32 v46, 16, v48
	v_and_b32_e32 v47, 0xffff0000, v48
	v_pk_add_f32 v[28:29], v[28:29], v[56:57]
	v_lshlrev_b32_e32 v48, 16, v49
	v_and_b32_e32 v49, 0xffff0000, v49
	v_pk_add_f32 v[46:47], v[24:25], v[46:47]
	v_cvt_pk_bf16_f32 v24, v28, v29
	v_cvt_pk_bf16_f32 v25, v30, v31
	v_pk_add_f32 v[48:49], v[26:27], v[48:49]
	v_cvt_pk_bf16_f32 v26, v46, v47
	s_nop 0
	v_cvt_pk_bf16_f32 v27, v48, v49
	global_store_dwordx4 v[54:55], v[24:27], off sc1
	s_nop 1
	v_mul_f32_e32 v24, v29, v29
	v_mul_f32_e32 v25, v31, v31
	v_fmac_f32_e32 v24, v28, v28
	v_fmac_f32_e32 v25, v30, v30
	v_add_f32_e32 v24, v24, v25
	v_mul_f32_e32 v25, v47, v47
	v_fmac_f32_e32 v25, v46, v46
	v_add_f32_e32 v24, v25, v24
	v_mul_f32_e32 v25, v49, v49
	v_fmac_f32_e32 v25, v48, v48
	v_add_f32_e32 v28, v25, v24
	s_waitcnt vmcnt(3)
	v_lshlrev_b32_e32 v24, 16, v50
	v_and_b32_e32 v25, 0xffff0000, v50
	v_lshlrev_b32_e32 v26, 16, v51
	v_and_b32_e32 v27, 0xffff0000, v51
	v_pk_add_f32 v[22:23], v[22:23], v[26:27]
	v_pk_add_f32 v[20:21], v[20:21], v[24:25]
	v_lshlrev_b32_e32 v24, 16, v52
	v_and_b32_e32 v25, 0xffff0000, v52
	v_lshlrev_b32_e32 v26, 16, v53
	v_and_b32_e32 v27, 0xffff0000, v53
	v_pk_add_f32 v[26:27], v[18:19], v[26:27]
	v_pk_add_f32 v[24:25], v[16:17], v[24:25]
	v_cvt_pk_bf16_f32 v16, v20, v21
	v_cvt_pk_bf16_f32 v17, v22, v23
	s_nop 0
	v_cvt_pk_bf16_f32 v18, v24, v25
	v_cvt_pk_bf16_f32 v19, v26, v27
	global_store_dwordx4 v[54:55], v[16:19], off offset:256 sc1
	s_nop 1
	v_mul_f32_e32 v18, v21, v21
	v_mul_f32_e32 v19, v23, v23
	v_mul_f32_e32 v17, v25, v25
	v_fmac_f32_e32 v18, v20, v20
	v_fmac_f32_e32 v19, v22, v22
	v_mul_f32_e32 v16, v27, v27
	v_fmac_f32_e32 v17, v24, v24
	v_add_f32_e32 v18, v18, v19
	v_fmac_f32_e32 v16, v26, v26
	v_add_f32_e32 v17, v17, v18
	v_add_f32_e32 v16, v16, v17
	v_add_f32_e32 v16, v28, v16
	ds_bpermute_b32 v17, v112, v16
	s_waitcnt lgkmcnt(0)
	v_add_f32_e32 v16, v16, v17
	ds_bpermute_b32 v17, v113, v16
	s_and_saveexec_b64 s[0:1], vcc
	s_cbranch_execz .LBB0_722
	s_waitcnt lgkmcnt(0)
	v_add_f32_e32 v18, v16, v17
	v_lshl_add_u64 v[16:17], v[44:45], 2, s[12:13]
	global_atomic_add_f32 v[16:17], v18, off
.LBB0_722:
	s_or_b64 exec, exec, s[0:1]
	s_waitcnt vmcnt(3)
	v_lshlrev_b32_e32 v16, 16, v36
	s_waitcnt lgkmcnt(0)
	v_and_b32_e32 v17, 0xffff0000, v36
	v_lshlrev_b32_e32 v18, 16, v37
	v_and_b32_e32 v19, 0xffff0000, v37
	v_pk_add_f32 v[12:13], v[12:13], v[16:17]
	v_lshlrev_b32_e32 v16, 16, v38
	v_and_b32_e32 v17, 0xffff0000, v38
	v_pk_add_f32 v[14:15], v[14:15], v[18:19]
	v_pk_add_f32 v[16:17], v[8:9], v[16:17]
	v_cvt_pk_bf16_f32 v8, v12, v13
	v_mul_f32_e32 v13, v13, v13
	v_fmac_f32_e32 v13, v12, v12
	v_mul_f32_e32 v12, v15, v15
	v_fmac_f32_e32 v12, v14, v14
	v_lshlrev_b32_e32 v18, 16, v39
	v_and_b32_e32 v19, 0xffff0000, v39
	v_add_f32_e32 v12, v13, v12
	v_mul_f32_e32 v13, v17, v17
	v_pk_add_f32 v[18:19], v[10:11], v[18:19]
	v_fmac_f32_e32 v13, v16, v16
	v_add_f32_e32 v12, v13, v12
	v_mul_f32_e32 v13, v19, v19
	v_fmac_f32_e32 v13, v18, v18
	v_cvt_pk_bf16_f32 v9, v14, v15
	v_cvt_pk_bf16_f32 v10, v16, v17
	v_add_f32_e32 v16, v13, v12
	s_waitcnt vmcnt(2)
	v_lshlrev_b32_e32 v12, 16, v32
	v_and_b32_e32 v13, 0xffff0000, v32
	v_lshlrev_b32_e32 v14, 16, v33
	v_and_b32_e32 v15, 0xffff0000, v33
	v_pk_add_f32 v[6:7], v[6:7], v[14:15]
	v_pk_add_f32 v[4:5], v[4:5], v[12:13]
	v_lshlrev_b32_e32 v12, 16, v34
	v_and_b32_e32 v13, 0xffff0000, v34
	v_lshlrev_b32_e32 v14, 16, v35
	v_and_b32_e32 v15, 0xffff0000, v35
	v_pk_add_f32 v[14:15], v[2:3], v[14:15]
	v_pk_add_f32 v[12:13], v[0:1], v[12:13]
	v_mul_f32_e32 v2, v5, v5
	v_mul_f32_e32 v3, v7, v7
	v_mul_f32_e32 v1, v13, v13
	v_fmac_f32_e32 v2, v4, v4
	v_fmac_f32_e32 v3, v6, v6
	v_mul_f32_e32 v0, v15, v15
	v_fmac_f32_e32 v1, v12, v12
	v_add_f32_e32 v2, v2, v3
	v_fmac_f32_e32 v0, v14, v14
	v_add_f32_e32 v1, v1, v2
	v_add_f32_e32 v0, v0, v1
	v_add_f32_e32 v3, v16, v0
	v_cvt_pk_bf16_f32 v11, v18, v19
	ds_bpermute_b32 v18, v112, v3
	v_lshl_add_u64 v[0:1], s[96:97], 0, v[42:43]
	v_lshl_add_u64 v[16:17], v[152:153], 1, v[0:1]
	global_store_dwordx4 v[16:17], v[8:11], off sc1
	v_cvt_pk_bf16_f32 v2, v4, v5
	s_waitcnt lgkmcnt(0)
	v_add_f32_e32 v0, v3, v18
	ds_bpermute_b32 v1, v113, v0
	v_cvt_pk_bf16_f32 v3, v6, v7
	v_cvt_pk_bf16_f32 v4, v12, v13
	v_cvt_pk_bf16_f32 v5, v14, v15
	global_store_dwordx4 v[16:17], v[2:5], off offset:256 sc1
	s_and_saveexec_b64 s[0:1], vcc
	s_cbranch_execz .LBB0_724
	v_lshl_add_u64 v[2:3], v[40:41], 2, s[12:13]
	s_waitcnt lgkmcnt(0)
	v_add_f32_e32 v0, v0, v1
	global_atomic_add_f32 v[2:3], v0, off

; __device__ __forceinline__ unsigned cvt_pk_bf16(float lo, float hi) { unsigned r; asm volatile("v_cvt_pk_bf16_f32 %0, %1, %2" : "=v"(r) : "v"(lo), "v"(hi)); return r; }
;     __device__ __forceinline__ void operator()(const f32x4 (&acc)[2][2][4][2], const Unit& u, int wr, int wc, int fr, int fq) const {
;     ...
;             for (int m = 0; m < 4; ++m) { const int row = row0 + ai * HALF + m * 16; bf16_t* rowp = G + (size_t)row * 2816 + col0;
;                 float* co = nullptr;
;                 if (row < 32768) { const int t = row & 8191; if (t >= 8190) co = outP + ((size_t)(row >> 13) * 2 + (t - 8190)) * 2816 + col0; }
;                 else { const int i = row & 7; if (i >= 6) co = outS + ((size_t)((row - 32768) >> 3) * 2 + (i - 6)) * 2816 + col0; }
;                 const float rs = rsqrtf(rsv[ai][m] * (1.f / 1024.f) + 1e-6f);
; #pragma unroll
;                 for (int bj = 0; bj < 2; ++bj) { const f32x4 v0 = acc[ai][bj][m][0] * rs, v1 = acc[ai][bj][m][1] * rs;
;                     u32x4 w; w.x = cvt_pk_bf16(v0[0], v0[1]); w.y = cvt_pk_bf16(v0[2], v0[3]); w.z = cvt_pk_bf16(v1[0], v1[1]); w.w = cvt_pk_bf16(v1[2], v1[3]);
;                     *(u32x4*)(rowp + bj * HALF) = w;
;                     if (co) { *(f32x4*)(co + bj * HALF) = v0; *(f32x4*)(co + bj * HALF + 4) = v1; } } }
.LBB0_836:
	s_or_b64 exec, exec, s[38:39]
	s_waitcnt vmcnt(0)
	v_fmamk_f32 v144, v144, 0x3a800000, v224
	v_cmp_gt_f32_e32 vcc, s71, v144
	v_mul_f32_e32 v145, 0x4b800000, v144
	v_readlane_b32 s38, v240, 12
	v_cndmask_b32_e32 v144, v144, v145, vcc
	v_rsq_f32_e32 v144, v144
	v_readlane_b32 s39, v240, 13
	v_mul_f32_e32 v145, 0x45800000, v144
	s_nop 0
	v_mov_b64_e32 v[142:143], s[38:39]
	v_mad_i64_i32 v[142:143], s[38:39], v2, s70, v[142:143]
	v_cndmask_b32_e32 v144, v144, v145, vcc
	v_lshl_add_u64 v[142:143], v[132:133], 1, v[142:143]
	v_cmp_ne_u64_e32 vcc, 0, v[140:141]
	v_pk_mul_f32 v[130:131], v[130:131], v[144:145] op_sel_hi:[1,0]
	v_pk_mul_f32 v[128:129], v[128:129], v[144:145] op_sel_hi:[1,0]
	v_pk_mul_f32 v[126:127], v[126:127], v[144:145] op_sel_hi:[1,0]
	v_pk_mul_f32 v[124:125], v[124:125], v[144:145] op_sel_hi:[1,0]
	v_cvt_pk_bf16_f32 v150, v128, v129
	v_cvt_pk_bf16_f32 v151, v130, v131
	s_nop 0
	v_cvt_pk_bf16_f32 v152, v124, v125
	v_cvt_pk_bf16_f32 v153, v126, v127
	global_store_dwordx4 v[142:143], v[150:153], off sc1
	s_and_saveexec_b64 s[38:39], vcc
	s_cbranch_execz .LBB0_838
	global_store_dwordx4 v[140:141], v[128:131], off sc1
	global_store_dwordx4 v[140:141], v[124:127], off offset:16 sc1
.LBB0_838:
	s_or_b64 exec, exec, s[38:39]
	v_mov_b32_e32 v145, v144
	v_mov_b32_e32 v124, v144
	v_mov_b32_e32 v125, v144
	v_pk_mul_f32 v[122:123], v[122:123], v[124:125]
	v_pk_mul_f32 v[120:121], v[120:121], v[144:145]
	v_pk_mul_f32 v[118:119], v[118:119], v[124:125]
	v_pk_mul_f32 v[116:117], v[116:117], v[144:145]
	v_cvt_pk_bf16_f32 v124, v120, v121
	v_cvt_pk_bf16_f32 v125, v122, v123
	s_nop 0
	v_cvt_pk_bf16_f32 v126, v116, v117
	v_cvt_pk_bf16_f32 v127, v118, v119
	global_store_dwordx4 v[142:143], v[124:127], off offset:256 sc1
	s_and_saveexec_b64 s[38:39], vcc
	s_cbranch_execz .LBB0_840
	global_store_dwordx4 v[140:141], v[120:123], off offset:512 sc1
	global_store_dwordx4 v[140:141], v[116:119], off offset:528 sc1

; __device__ __forceinline__ unsigned cvt_pk_bf16(float lo, float hi) { unsigned r; asm volatile("v_cvt_pk_bf16_f32 %0, %1, %2" : "=v"(r) : "v"(lo), "v"(hi)); return r; }
;     __device__ __forceinline__ void operator()(const f32x4 (&acc)[2][2][4][2], const Unit& u, int wr, int wc, int fr, int fq) const {
;     ...
;             for (int m = 0; m < 4; ++m) { const int row = row0 + ai * HALF + m * 16; bf16_t* rowp = G + (size_t)row * 2816 + col0;
;                 float* co = nullptr;
;                 if (row < 32768) { const int t = row & 8191; if (t >= 8190) co = outP + ((size_t)(row >> 13) * 2 + (t - 8190)) * 2816 + col0; }
;                 else { const int i = row & 7; if (i >= 6) co = outS + ((size_t)((row - 32768) >> 3) * 2 + (i - 6)) * 2816 + col0; }
;                 const float rs = rsqrtf(rsv[ai][m] * (1.f / 1024.f) + 1e-6f);
; #pragma unroll
;                 for (int bj = 0; bj < 2; ++bj) { const f32x4 v0 = acc[ai][bj][m][0] * rs, v1 = acc[ai][bj][m][1] * rs;
;                     u32x4 w; w.x = cvt_pk_bf16(v0[0], v0[1]); w.y = cvt_pk_bf16(v0[2], v0[3]); w.z = cvt_pk_bf16(v1[0], v1[1]); w.w = cvt_pk_bf16(v1[2], v1[3]);
;                     *(u32x4*)(rowp + bj * HALF) = w;
;                     if (co) { *(f32x4*)(co + bj * HALF) = v0; *(f32x4*)(co + bj * HALF + 4) = v1; } } }
.LBB0_848:
	s_or_b64 exec, exec, s[38:39]
	v_fmamk_f32 v120, v148, 0x3a800000, v224
	v_cmp_gt_f32_e32 vcc, s71, v120
	v_mul_f32_e32 v121, 0x4b800000, v120
	v_readlane_b32 s38, v240, 12
	v_cndmask_b32_e32 v120, v120, v121, vcc
	v_rsq_f32_e32 v120, v120
	v_readlane_b32 s39, v240, 13
	v_mul_f32_e32 v121, 0x45800000, v120
	s_nop 0
	v_mov_b64_e32 v[118:119], s[38:39]
	v_mad_i64_i32 v[118:119], s[38:39], v138, s70, v[118:119]
	v_cndmask_b32_e32 v120, v120, v121, vcc
	v_lshl_add_u64 v[118:119], v[132:133], 1, v[118:119]
	v_cmp_ne_u64_e32 vcc, 0, v[116:117]
	v_pk_mul_f32 v[114:115], v[114:115], v[120:121] op_sel_hi:[1,0]
	v_pk_mul_f32 v[112:113], v[112:113], v[120:121] op_sel_hi:[1,0]
	v_pk_mul_f32 v[110:111], v[110:111], v[120:121] op_sel_hi:[1,0]
	v_pk_mul_f32 v[108:109], v[108:109], v[120:121] op_sel_hi:[1,0]
	v_cvt_pk_bf16_f32 v122, v112, v113
	v_cvt_pk_bf16_f32 v123, v114, v115
	s_nop 0
	v_cvt_pk_bf16_f32 v124, v108, v109
	v_cvt_pk_bf16_f32 v125, v110, v111
	global_store_dwordx4 v[118:119], v[122:125], off sc1
	s_and_saveexec_b64 s[38:39], vcc
	s_cbranch_execz .LBB0_850
	global_store_dwordx4 v[116:117], v[112:115], off sc1
	global_store_dwordx4 v[116:117], v[108:111], off offset:16 sc1
.LBB0_850:
	s_or_b64 exec, exec, s[38:39]
	v_mov_b32_e32 v121, v120
	v_mov_b32_e32 v108, v120
	v_mov_b32_e32 v109, v120
	v_pk_mul_f32 v[106:107], v[106:107], v[108:109]
	v_pk_mul_f32 v[104:105], v[104:105], v[120:121]
	v_pk_mul_f32 v[102:103], v[102:103], v[108:109]
	v_pk_mul_f32 v[100:101], v[100:101], v[120:121]
	v_cvt_pk_bf16_f32 v108, v104, v105
	v_cvt_pk_bf16_f32 v109, v106, v107
	s_nop 0
	v_cvt_pk_bf16_f32 v110, v100, v101
	v_cvt_pk_bf16_f32 v111, v102, v103
	global_store_dwordx4 v[118:119], v[108:111], off offset:256 sc1
	s_and_saveexec_b64 s[38:39], vcc
	s_cbranch_execz .LBB0_852
	global_store_dwordx4 v[116:117], v[104:107], off offset:512 sc1
	global_store_dwordx4 v[116:117], v[100:103], off offset:528 sc1

; __device__ __forceinline__ unsigned cvt_pk_bf16(float lo, float hi) { unsigned r; asm volatile("v_cvt_pk_bf16_f32 %0, %1, %2" : "=v"(r) : "v"(lo), "v"(hi)); return r; }
;     __device__ __forceinline__ void operator()(const f32x4 (&acc)[2][2][4][2], const Unit& u, int wr, int wc, int fr, int fq) const {
;     ...
;             for (int m = 0; m < 4; ++m) { const int row = row0 + ai * HALF + m * 16; bf16_t* rowp = G + (size_t)row * 2816 + col0;
;                 float* co = nullptr;
;                 if (row < 32768) { const int t = row & 8191; if (t >= 8190) co = outP + ((size_t)(row >> 13) * 2 + (t - 8190)) * 2816 + col0; }
;                 else { const int i = row & 7; if (i >= 6) co = outS + ((size_t)((row - 32768) >> 3) * 2 + (i - 6)) * 2816 + col0; }
;                 const float rs = rsqrtf(rsv[ai][m] * (1.f / 1024.f) + 1e-6f);
; #pragma unroll
;                 for (int bj = 0; bj < 2; ++bj) { const f32x4 v0 = acc[ai][bj][m][0] * rs, v1 = acc[ai][bj][m][1] * rs;
;                     u32x4 w; w.x = cvt_pk_bf16(v0[0], v0[1]); w.y = cvt_pk_bf16(v0[2], v0[3]); w.z = cvt_pk_bf16(v1[0], v1[1]); w.w = cvt_pk_bf16(v1[2], v1[3]);
;                     *(u32x4*)(rowp + bj * HALF) = w;
;                     if (co) { *(f32x4*)(co + bj * HALF) = v0; *(f32x4*)(co + bj * HALF + 4) = v1; } } }
.LBB0_860:
	s_or_b64 exec, exec, s[38:39]
	v_fmamk_f32 v104, v147, 0x3a800000, v224
	v_cmp_gt_f32_e32 vcc, s71, v104
	v_mul_f32_e32 v105, 0x4b800000, v104
	v_readlane_b32 s38, v240, 12
	v_cndmask_b32_e32 v104, v104, v105, vcc
	v_rsq_f32_e32 v104, v104
	v_readlane_b32 s39, v240, 13
	v_mul_f32_e32 v105, 0x45800000, v104
	s_nop 0
	v_mov_b64_e32 v[102:103], s[38:39]
	v_mad_i64_i32 v[102:103], s[38:39], v136, s70, v[102:103]
	v_cndmask_b32_e32 v104, v104, v105, vcc
	v_lshl_add_u64 v[102:103], v[132:133], 1, v[102:103]
	v_cmp_ne_u64_e32 vcc, 0, v[100:101]
	v_pk_mul_f32 v[98:99], v[98:99], v[104:105] op_sel_hi:[1,0]
	v_pk_mul_f32 v[96:97], v[96:97], v[104:105] op_sel_hi:[1,0]
	v_pk_mul_f32 v[94:95], v[94:95], v[104:105] op_sel_hi:[1,0]
	v_pk_mul_f32 v[92:93], v[92:93], v[104:105] op_sel_hi:[1,0]
	v_cvt_pk_bf16_f32 v106, v96, v97
	v_cvt_pk_bf16_f32 v107, v98, v99
	s_nop 0
	v_cvt_pk_bf16_f32 v108, v92, v93
	v_cvt_pk_bf16_f32 v109, v94, v95
	global_store_dwordx4 v[102:103], v[106:109], off sc1
	s_and_saveexec_b64 s[38:39], vcc
	s_cbranch_execz .LBB0_862
	global_store_dwordx4 v[100:101], v[96:99], off sc1
	global_store_dwordx4 v[100:101], v[92:95], off offset:16 sc1
.LBB0_862:
	s_or_b64 exec, exec, s[38:39]
	v_mov_b32_e32 v105, v104
	v_mov_b32_e32 v92, v104
	v_mov_b32_e32 v93, v104
	v_pk_mul_f32 v[90:91], v[90:91], v[92:93]
	v_pk_mul_f32 v[88:89], v[88:89], v[104:105]
	v_pk_mul_f32 v[86:87], v[86:87], v[92:93]
	v_pk_mul_f32 v[84:85], v[84:85], v[104:105]
	v_cvt_pk_bf16_f32 v92, v88, v89
	v_cvt_pk_bf16_f32 v93, v90, v91
	s_nop 0
	v_cvt_pk_bf16_f32 v94, v84, v85
	v_cvt_pk_bf16_f32 v95, v86, v87
	global_store_dwordx4 v[102:103], v[92:95], off offset:256 sc1
	s_and_saveexec_b64 s[38:39], vcc
	s_cbranch_execz .LBB0_864
	global_store_dwordx4 v[100:101], v[88:91], off offset:512 sc1
	global_store_dwordx4 v[100:101], v[84:87], off offset:528 sc1

; __device__ __forceinline__ unsigned cvt_pk_bf16(float lo, float hi) { unsigned r; asm volatile("v_cvt_pk_bf16_f32 %0, %1, %2" : "=v"(r) : "v"(lo), "v"(hi)); return r; }
;     __device__ __forceinline__ void operator()(const f32x4 (&acc)[2][2][4][2], const Unit& u, int wr, int wc, int fr, int fq) const {
;     ...
;             for (int m = 0; m < 4; ++m) { const int row = row0 + ai * HALF + m * 16; bf16_t* rowp = G + (size_t)row * 2816 + col0;
;                 float* co = nullptr;
;                 if (row < 32768) { const int t = row & 8191; if (t >= 8190) co = outP + ((size_t)(row >> 13) * 2 + (t - 8190)) * 2816 + col0; }
;                 else { const int i = row & 7; if (i >= 6) co = outS + ((size_t)((row - 32768) >> 3) * 2 + (i - 6)) * 2816 + col0; }
;                 const float rs = rsqrtf(rsv[ai][m] * (1.f / 1024.f) + 1e-6f);
; #pragma unroll
;                 for (int bj = 0; bj < 2; ++bj) { const f32x4 v0 = acc[ai][bj][m][0] * rs, v1 = acc[ai][bj][m][1] * rs;
;                     u32x4 w; w.x = cvt_pk_bf16(v0[0], v0[1]); w.y = cvt_pk_bf16(v0[2], v0[3]); w.z = cvt_pk_bf16(v1[0], v1[1]); w.w = cvt_pk_bf16(v1[2], v1[3]);
;                     *(u32x4*)(rowp + bj * HALF) = w;
;                     if (co) { *(f32x4*)(co + bj * HALF) = v0; *(f32x4*)(co + bj * HALF + 4) = v1; } } }
.LBB0_872:
	s_or_b64 exec, exec, s[38:39]
	v_fmamk_f32 v88, v146, 0x3a800000, v224
	v_cmp_gt_f32_e32 vcc, s71, v88
	v_mul_f32_e32 v89, 0x4b800000, v88
	v_readlane_b32 s38, v240, 12
	v_cndmask_b32_e32 v88, v88, v89, vcc
	v_rsq_f32_e32 v88, v88
	v_readlane_b32 s39, v240, 13
	v_mul_f32_e32 v89, 0x45800000, v88
	s_nop 0
	v_mov_b64_e32 v[86:87], s[38:39]
	v_mad_i64_i32 v[86:87], s[38:39], v134, s70, v[86:87]
	v_cndmask_b32_e32 v88, v88, v89, vcc
	v_lshl_add_u64 v[86:87], v[132:133], 1, v[86:87]
	v_cmp_ne_u64_e32 vcc, 0, v[84:85]
	v_pk_mul_f32 v[82:83], v[82:83], v[88:89] op_sel_hi:[1,0]
	v_pk_mul_f32 v[80:81], v[80:81], v[88:89] op_sel_hi:[1,0]
	v_pk_mul_f32 v[78:79], v[78:79], v[88:89] op_sel_hi:[1,0]
	v_pk_mul_f32 v[76:77], v[76:77], v[88:89] op_sel_hi:[1,0]
	v_cvt_pk_bf16_f32 v90, v80, v81
	v_cvt_pk_bf16_f32 v91, v82, v83
	s_nop 0
	v_cvt_pk_bf16_f32 v92, v76, v77
	v_cvt_pk_bf16_f32 v93, v78, v79
	global_store_dwordx4 v[86:87], v[90:93], off sc1
	s_and_saveexec_b64 s[38:39], vcc
	s_cbranch_execz .LBB0_874
	global_store_dwordx4 v[84:85], v[80:83], off sc1
	global_store_dwordx4 v[84:85], v[76:79], off offset:16 sc1
.LBB0_874:
	s_or_b64 exec, exec, s[38:39]
	v_mov_b32_e32 v89, v88
	v_mov_b32_e32 v76, v88
	v_mov_b32_e32 v77, v88
	v_pk_mul_f32 v[74:75], v[74:75], v[76:77]
	v_pk_mul_f32 v[72:73], v[72:73], v[88:89]
	v_pk_mul_f32 v[70:71], v[70:71], v[76:77]
	v_pk_mul_f32 v[68:69], v[68:69], v[88:89]
	v_cvt_pk_bf16_f32 v76, v72, v73
	v_cvt_pk_bf16_f32 v77, v74, v75
	s_nop 0
	v_cvt_pk_bf16_f32 v78, v68, v69
	v_cvt_pk_bf16_f32 v79, v70, v71
	global_store_dwordx4 v[86:87], v[76:79], off offset:256 sc1
	s_and_saveexec_b64 s[38:39], vcc
	s_cbranch_execz .LBB0_925
	global_store_dwordx4 v[84:85], v[72:75], off offset:512 sc1
	global_store_dwordx4 v[84:85], v[68:71], off offset:528 sc1
	s_or_b64 exec, exec, s[38:39]
	s_and_b64 vcc, exec, s[8:9]
	s_cbranch_vccnz .LBB0_926

; __device__ __forceinline__ unsigned cvt_pk_bf16(float lo, float hi) { unsigned r; asm volatile("v_cvt_pk_bf16_f32 %0, %1, %2" : "=v"(r) : "v"(lo), "v"(hi)); return r; }
;     __device__ __forceinline__ void operator()(const f32x4 (&acc)[2][2][4][2], const Unit& u, int wr, int wc, int fr, int fq) const {
;     ...
;             for (int m = 0; m < 4; ++m) { const int row = row0 + ai * HALF + m * 16; bf16_t* rowp = G + (size_t)row * 2816 + col0;
;                 float* co = nullptr;
;                 if (row < 32768) { const int t = row & 8191; if (t >= 8190) co = outP + ((size_t)(row >> 13) * 2 + (t - 8190)) * 2816 + col0; }
;                 else { const int i = row & 7; if (i >= 6) co = outS + ((size_t)((row - 32768) >> 3) * 2 + (i - 6)) * 2816 + col0; }
;                 const float rs = rsqrtf(rsv[ai][m] * (1.f / 1024.f) + 1e-6f);
; #pragma unroll
;                 for (int bj = 0; bj < 2; ++bj) { const f32x4 v0 = acc[ai][bj][m][0] * rs, v1 = acc[ai][bj][m][1] * rs;
;                     u32x4 w; w.x = cvt_pk_bf16(v0[0], v0[1]); w.y = cvt_pk_bf16(v0[2], v0[3]); w.z = cvt_pk_bf16(v1[0], v1[1]); w.w = cvt_pk_bf16(v1[2], v1[3]);
;                     *(u32x4*)(rowp + bj * HALF) = w;
;                     if (co) { *(f32x4*)(co + bj * HALF) = v0; *(f32x4*)(co + bj * HALF + 4) = v1; } } }
.LBB0_884:
	s_or_b64 exec, exec, s[8:9]
	v_readlane_b32 s8, v240, 12
	v_readlane_b32 s9, v240, 13
	s_nop 1
	v_mov_b64_e32 v[72:73], s[8:9]
	v_mad_i64_i32 v[70:71], s[8:9], v70, s70, v[72:73]
	v_fmamk_f32 v72, v139, 0x3a800000, v224
	v_cmp_gt_f32_e32 vcc, s71, v72
	v_mul_f32_e32 v73, 0x4b800000, v72
	v_lshl_add_u64 v[70:71], v[132:133], 1, v[70:71]
	v_cndmask_b32_e32 v72, v72, v73, vcc
	v_rsq_f32_e32 v72, v72
	s_nop 0
	v_mul_f32_e32 v73, 0x45800000, v72
	v_cndmask_b32_e32 v72, v72, v73, vcc
	v_cmp_ne_u64_e32 vcc, 0, v[68:69]
	v_pk_mul_f32 v[66:67], v[66:67], v[72:73] op_sel_hi:[1,0]
	v_pk_mul_f32 v[64:65], v[64:65], v[72:73] op_sel_hi:[1,0]
	v_pk_mul_f32 v[62:63], v[62:63], v[72:73] op_sel_hi:[1,0]
	v_pk_mul_f32 v[60:61], v[60:61], v[72:73] op_sel_hi:[1,0]
	v_cvt_pk_bf16_f32 v74, v64, v65
	v_cvt_pk_bf16_f32 v75, v66, v67
	s_nop 0
	v_cvt_pk_bf16_f32 v76, v60, v61
	v_cvt_pk_bf16_f32 v77, v62, v63
	global_store_dwordx4 v[70:71], v[74:77], off sc1
	s_and_saveexec_b64 s[8:9], vcc
	s_cbranch_execz .LBB0_886
	global_store_dwordx4 v[68:69], v[64:67], off sc1
	global_store_dwordx4 v[68:69], v[60:63], off offset:16 sc1
.LBB0_886:
	s_or_b64 exec, exec, s[8:9]
	v_mov_b32_e32 v73, v72
	v_mov_b32_e32 v60, v72
	v_mov_b32_e32 v61, v72
	v_pk_mul_f32 v[58:59], v[58:59], v[60:61]
	v_pk_mul_f32 v[56:57], v[56:57], v[72:73]
	v_pk_mul_f32 v[54:55], v[54:55], v[60:61]
	v_pk_mul_f32 v[52:53], v[52:53], v[72:73]
	v_cvt_pk_bf16_f32 v60, v56, v57
	v_cvt_pk_bf16_f32 v61, v58, v59
	s_nop 0
	v_cvt_pk_bf16_f32 v62, v52, v53
	v_cvt_pk_bf16_f32 v63, v54, v55
	global_store_dwordx4 v[70:71], v[60:63], off offset:256 sc1
	s_and_saveexec_b64 s[8:9], vcc
	s_cbranch_execz .LBB0_888
	global_store_dwordx4 v[68:69], v[56:59], off offset:512 sc1
	global_store_dwordx4 v[68:69], v[52:55], off offset:528 sc1

; __device__ __forceinline__ unsigned cvt_pk_bf16(float lo, float hi) { unsigned r; asm volatile("v_cvt_pk_bf16_f32 %0, %1, %2" : "=v"(r) : "v"(lo), "v"(hi)); return r; }
;     __device__ __forceinline__ void operator()(const f32x4 (&acc)[2][2][4][2], const Unit& u, int wr, int wc, int fr, int fq) const {
;     ...
;             for (int m = 0; m < 4; ++m) { const int row = row0 + ai * HALF + m * 16; bf16_t* rowp = G + (size_t)row * 2816 + col0;
;                 float* co = nullptr;
;                 if (row < 32768) { const int t = row & 8191; if (t >= 8190) co = outP + ((size_t)(row >> 13) * 2 + (t - 8190)) * 2816 + col0; }
;                 else { const int i = row & 7; if (i >= 6) co = outS + ((size_t)((row - 32768) >> 3) * 2 + (i - 6)) * 2816 + col0; }
;                 const float rs = rsqrtf(rsv[ai][m] * (1.f / 1024.f) + 1e-6f);
; #pragma unroll
;                 for (int bj = 0; bj < 2; ++bj) { const f32x4 v0 = acc[ai][bj][m][0] * rs, v1 = acc[ai][bj][m][1] * rs;
;                     u32x4 w; w.x = cvt_pk_bf16(v0[0], v0[1]); w.y = cvt_pk_bf16(v0[2], v0[3]); w.z = cvt_pk_bf16(v1[0], v1[1]); w.w = cvt_pk_bf16(v1[2], v1[3]);
;                     *(u32x4*)(rowp + bj * HALF) = w;
;                     if (co) { *(f32x4*)(co + bj * HALF) = v0; *(f32x4*)(co + bj * HALF + 4) = v1; } } }
.LBB0_896:
	s_or_b64 exec, exec, s[8:9]
	v_readlane_b32 s8, v240, 12
	v_readlane_b32 s9, v240, 13
	s_nop 1
	v_mov_b64_e32 v[56:57], s[8:9]
	v_mad_i64_i32 v[54:55], s[8:9], v54, s70, v[56:57]
	v_fmamk_f32 v56, v137, 0x3a800000, v224
	v_cmp_gt_f32_e32 vcc, s71, v56
	v_mul_f32_e32 v57, 0x4b800000, v56
	v_lshl_add_u64 v[54:55], v[132:133], 1, v[54:55]
	v_cndmask_b32_e32 v56, v56, v57, vcc
	v_rsq_f32_e32 v56, v56
	s_nop 0
	v_mul_f32_e32 v57, 0x45800000, v56
	v_cndmask_b32_e32 v56, v56, v57, vcc
	v_cmp_ne_u64_e32 vcc, 0, v[52:53]
	v_pk_mul_f32 v[50:51], v[50:51], v[56:57] op_sel_hi:[1,0]
	v_pk_mul_f32 v[48:49], v[48:49], v[56:57] op_sel_hi:[1,0]
	v_pk_mul_f32 v[46:47], v[46:47], v[56:57] op_sel_hi:[1,0]
	v_pk_mul_f32 v[44:45], v[44:45], v[56:57] op_sel_hi:[1,0]
	v_cvt_pk_bf16_f32 v58, v48, v49
	v_cvt_pk_bf16_f32 v59, v50, v51
	s_nop 0
	v_cvt_pk_bf16_f32 v60, v44, v45
	v_cvt_pk_bf16_f32 v61, v46, v47
	global_store_dwordx4 v[54:55], v[58:61], off sc1
	s_and_saveexec_b64 s[8:9], vcc
	s_cbranch_execz .LBB0_898
	global_store_dwordx4 v[52:53], v[48:51], off sc1
	global_store_dwordx4 v[52:53], v[44:47], off offset:16 sc1
.LBB0_898:
	s_or_b64 exec, exec, s[8:9]
	v_mov_b32_e32 v57, v56
	v_mov_b32_e32 v44, v56
	v_mov_b32_e32 v45, v56
	v_pk_mul_f32 v[42:43], v[42:43], v[44:45]
	v_pk_mul_f32 v[40:41], v[40:41], v[56:57]
	v_pk_mul_f32 v[38:39], v[38:39], v[44:45]
	v_pk_mul_f32 v[36:37], v[36:37], v[56:57]
	v_cvt_pk_bf16_f32 v44, v40, v41
	v_cvt_pk_bf16_f32 v45, v42, v43
	s_nop 0
	v_cvt_pk_bf16_f32 v46, v36, v37
	v_cvt_pk_bf16_f32 v47, v38, v39
	global_store_dwordx4 v[54:55], v[44:47], off offset:256 sc1
	s_and_saveexec_b64 s[8:9], vcc
	s_cbranch_execz .LBB0_900
	global_store_dwordx4 v[52:53], v[40:43], off offset:512 sc1
	global_store_dwordx4 v[52:53], v[36:39], off offset:528 sc1

; __device__ __forceinline__ unsigned cvt_pk_bf16(float lo, float hi) { unsigned r; asm volatile("v_cvt_pk_bf16_f32 %0, %1, %2" : "=v"(r) : "v"(lo), "v"(hi)); return r; }
;     __device__ __forceinline__ void operator()(const f32x4 (&acc)[2][2][4][2], const Unit& u, int wr, int wc, int fr, int fq) const {
;     ...
;             for (int m = 0; m < 4; ++m) { const int row = row0 + ai * HALF + m * 16; bf16_t* rowp = G + (size_t)row * 2816 + col0;
;                 float* co = nullptr;
;                 if (row < 32768) { const int t = row & 8191; if (t >= 8190) co = outP + ((size_t)(row >> 13) * 2 + (t - 8190)) * 2816 + col0; }
;                 else { const int i = row & 7; if (i >= 6) co = outS + ((size_t)((row - 32768) >> 3) * 2 + (i - 6)) * 2816 + col0; }
;                 const float rs = rsqrtf(rsv[ai][m] * (1.f / 1024.f) + 1e-6f);
; #pragma unroll
;                 for (int bj = 0; bj < 2; ++bj) { const f32x4 v0 = acc[ai][bj][m][0] * rs, v1 = acc[ai][bj][m][1] * rs;
;                     u32x4 w; w.x = cvt_pk_bf16(v0[0], v0[1]); w.y = cvt_pk_bf16(v0[2], v0[3]); w.z = cvt_pk_bf16(v1[0], v1[1]); w.w = cvt_pk_bf16(v1[2], v1[3]);
;                     *(u32x4*)(rowp + bj * HALF) = w;
;                     if (co) { *(f32x4*)(co + bj * HALF) = v0; *(f32x4*)(co + bj * HALF + 4) = v1; } } }
.LBB0_908:
	s_or_b64 exec, exec, s[8:9]
	v_readlane_b32 s8, v240, 12
	v_readlane_b32 s9, v240, 13
	s_nop 1
	v_mov_b64_e32 v[40:41], s[8:9]
	v_mad_i64_i32 v[38:39], s[8:9], v38, s70, v[40:41]
	v_fmamk_f32 v40, v135, 0x3a800000, v224
	v_cmp_gt_f32_e32 vcc, s71, v40
	v_mul_f32_e32 v41, 0x4b800000, v40
	v_lshl_add_u64 v[38:39], v[132:133], 1, v[38:39]
	v_cndmask_b32_e32 v40, v40, v41, vcc
	v_rsq_f32_e32 v40, v40
	s_nop 0
	v_mul_f32_e32 v41, 0x45800000, v40
	v_cndmask_b32_e32 v40, v40, v41, vcc
	v_cmp_ne_u64_e32 vcc, 0, v[36:37]
	v_pk_mul_f32 v[34:35], v[34:35], v[40:41] op_sel_hi:[1,0]
	v_pk_mul_f32 v[32:33], v[32:33], v[40:41] op_sel_hi:[1,0]
	v_pk_mul_f32 v[30:31], v[30:31], v[40:41] op_sel_hi:[1,0]
	v_pk_mul_f32 v[28:29], v[28:29], v[40:41] op_sel_hi:[1,0]
	v_cvt_pk_bf16_f32 v42, v32, v33
	v_cvt_pk_bf16_f32 v43, v34, v35
	s_nop 0
	v_cvt_pk_bf16_f32 v44, v28, v29
	v_cvt_pk_bf16_f32 v45, v30, v31
	global_store_dwordx4 v[38:39], v[42:45], off sc1
	s_and_saveexec_b64 s[8:9], vcc
	s_cbranch_execz .LBB0_910
	global_store_dwordx4 v[36:37], v[32:35], off sc1
	global_store_dwordx4 v[36:37], v[28:31], off offset:16 sc1
.LBB0_910:
	s_or_b64 exec, exec, s[8:9]
	v_mov_b32_e32 v41, v40
	v_mov_b32_e32 v28, v40
	v_mov_b32_e32 v29, v40
	v_pk_mul_f32 v[26:27], v[26:27], v[28:29]
	v_pk_mul_f32 v[24:25], v[24:25], v[40:41]
	v_pk_mul_f32 v[22:23], v[22:23], v[28:29]
	v_pk_mul_f32 v[20:21], v[20:21], v[40:41]
	v_cvt_pk_bf16_f32 v28, v24, v25
	v_cvt_pk_bf16_f32 v29, v26, v27
	s_nop 0
	v_cvt_pk_bf16_f32 v30, v20, v21
	v_cvt_pk_bf16_f32 v31, v22, v23
	global_store_dwordx4 v[38:39], v[28:31], off offset:256 sc1
	s_and_saveexec_b64 s[8:9], vcc
	s_cbranch_execz .LBB0_912
	global_store_dwordx4 v[36:37], v[24:27], off offset:512 sc1
	global_store_dwordx4 v[36:37], v[20:23], off offset:528 sc1

; __device__ __forceinline__ unsigned cvt_pk_bf16(float lo, float hi) { unsigned r; asm volatile("v_cvt_pk_bf16_f32 %0, %1, %2" : "=v"(r) : "v"(lo), "v"(hi)); return r; }
;     __device__ __forceinline__ void operator()(const f32x4 (&acc)[2][2][4][2], const Unit& u, int wr, int wc, int fr, int fq) const {
;     ...
;             for (int m = 0; m < 4; ++m) { const int row = row0 + ai * HALF + m * 16; bf16_t* rowp = G + (size_t)row * 2816 + col0;
;                 float* co = nullptr;
;                 if (row < 32768) { const int t = row & 8191; if (t >= 8190) co = outP + ((size_t)(row >> 13) * 2 + (t - 8190)) * 2816 + col0; }
;                 else { const int i = row & 7; if (i >= 6) co = outS + ((size_t)((row - 32768) >> 3) * 2 + (i - 6)) * 2816 + col0; }
;                 const float rs = rsqrtf(rsv[ai][m] * (1.f / 1024.f) + 1e-6f);
; #pragma unroll
;                 for (int bj = 0; bj < 2; ++bj) { const f32x4 v0 = acc[ai][bj][m][0] * rs, v1 = acc[ai][bj][m][1] * rs;
;                     u32x4 w; w.x = cvt_pk_bf16(v0[0], v0[1]); w.y = cvt_pk_bf16(v0[2], v0[3]); w.z = cvt_pk_bf16(v1[0], v1[1]); w.w = cvt_pk_bf16(v1[2], v1[3]);
;                     *(u32x4*)(rowp + bj * HALF) = w;
;                     if (co) { *(f32x4*)(co + bj * HALF) = v0; *(f32x4*)(co + bj * HALF + 4) = v1; } } }
.LBB0_920:
	s_or_b64 exec, exec, s[0:1]
	v_readlane_b32 s0, v240, 12
	v_readlane_b32 s1, v240, 13
	v_fmamk_f32 v1, v1, 0x3a800000, v224
	v_cmp_gt_f32_e32 vcc, s71, v1
	v_mov_b64_e32 v[22:23], s[0:1]
	v_mad_i64_i32 v[2:3], s[0:1], v2, s70, v[22:23]
	v_mul_f32_e32 v22, 0x4b800000, v1
	v_cndmask_b32_e32 v1, v1, v22, vcc
	v_rsq_f32_e32 v1, v1
	v_lshl_add_u64 v[2:3], v[132:133], 1, v[2:3]
	v_mul_f32_e32 v22, 0x45800000, v1
	v_cndmask_b32_e32 v22, v1, v22, vcc
	v_cmp_ne_u64_e32 vcc, 0, v[20:21]
	v_pk_mul_f32 v[18:19], v[18:19], v[22:23] op_sel_hi:[1,0]
	v_pk_mul_f32 v[16:17], v[16:17], v[22:23] op_sel_hi:[1,0]
	v_pk_mul_f32 v[14:15], v[14:15], v[22:23] op_sel_hi:[1,0]
	v_pk_mul_f32 v[12:13], v[12:13], v[22:23] op_sel_hi:[1,0]
	v_cvt_pk_bf16_f32 v24, v16, v17
	v_cvt_pk_bf16_f32 v25, v18, v19
	s_nop 0
	v_cvt_pk_bf16_f32 v26, v12, v13
	v_cvt_pk_bf16_f32 v27, v14, v15
	global_store_dwordx4 v[2:3], v[24:27], off sc1
	s_and_saveexec_b64 s[0:1], vcc
	s_cbranch_execz .LBB0_922
	global_store_dwordx4 v[20:21], v[16:19], off sc1
	global_store_dwordx4 v[20:21], v[12:15], off offset:16 sc1
.LBB0_922:
	s_or_b64 exec, exec, s[0:1]
	v_mov_b32_e32 v23, v22
	v_mov_b32_e32 v12, v22
	v_mov_b32_e32 v13, v22
	v_pk_mul_f32 v[10:11], v[10:11], v[12:13]
	v_pk_mul_f32 v[8:9], v[8:9], v[22:23]
	v_pk_mul_f32 v[6:7], v[6:7], v[12:13]
	v_pk_mul_f32 v[4:5], v[4:5], v[22:23]
	v_cvt_pk_bf16_f32 v12, v8, v9
	v_cvt_pk_bf16_f32 v13, v10, v11
	s_nop 0
	v_cvt_pk_bf16_f32 v14, v4, v5
	v_cvt_pk_bf16_f32 v15, v6, v7
	global_store_dwordx4 v[2:3], v[12:15], off offset:256 sc1
	s_and_saveexec_b64 s[0:1], vcc
	s_cbranch_execz .LBB0_924
	global_store_dwordx4 v[20:21], v[8:11], off offset:512 sc1
	global_store_dwordx4 v[20:21], v[4:7], off offset:528 sc1

;     static __device__ __forceinline__ void unpk4(const u32x2 w, float (&o)[4]) { o[0] = bf_lo(w.x); o[1] = bf_hi(w.x); o[2] = bf_lo(w.y); o[3] = bf_hi(w.y); }
;     template <int N> static __device__ __forceinline__ u32x2 dpp_prev(const u32x2 pv, const u32x2 cur) { u32x2 r; r.x = dpp_prev1<N>(pv.x, cur.x); r.y = dpp_prev1<N>(pv.y, cur.y); return r; }
;     __device__ __forceinline__ void operator()(const f32x4 (&acc)[2][2][4][2], const Unit& u, int wr, int wc, int fr, int fq) const {
;     ...
;         float rs8[2][4];
; #pragma unroll
;         for (int ai = 0; ai < 2; ++ai)
; #pragma unroll
;             for (int m = 0; m < 4; ++m) rs8[ai][m] = rsqrtf(SS[u.rb + (u.half ? 0 : ai * HALF) + wr * 64 + fr + 16 * m] * (1.f / 1024.f) + 1e-6f);
;         if (u.pm < 128) {
;     ...
;           for (int hv = 0; hv < 2; ++hv) {
;             const int col = u.pn * BM + bj * HALF + wc * 32 + 8 * fq + 4 * hv;
;             float w0[4], w1[4], w2[4], bb[4];
;             ld4f(cw + col, w0); ld4f(cw + 2816 + col, w1); ld4f(cw + 2 * 2816 + col, w2); ld4f(cb + col, bb);
;             {
;                 const int i = fr & 7;
;                 u32x2 gq[4];
; #pragma unroll
;                 for (int m = 0; m < 4; ++m) { const int row = row0 + m * 16; gq[m] = *(const u32x2*)(G + (size_t)row * 2816 + col); }
; #pragma unroll
;                 for (int mh = 0; mh < 4; mh += 2) {
;                 f32x4 c0[4], c1[4];
; #pragma unroll
;                 for (int m = mh; m < mh + 2; ++m) { const int row = row0 + m * 16; const float* cx = ctx + (size_t)((row - 32768) >> 3) * 2 * 2816 + col;
;                     c0[m] = *(const f32x4*)cx; c1[m] = *(const f32x4*)(cx + 2816); }
; #pragma unroll
;                 for (int m = mh; m < mh + 2; ++m) { const int row = row0 + m * 16; const u32x2 cur = gq[m];
;                     const u32x2 q1 = dpp_prev<1>(cur, cur), q2 = dpp_prev<2>(cur, cur);
;                     float g0[4], g1[4], g2[4]; unpk4(cur, g0); unpk4(q1, g1); unpk4(q2, g2);
; #pragma unroll
;                     for (int j = 0; j < 4; ++j) { const float x1 = c1[m][j], x0 = c0[m][j];
;                         if (i < 1) g1[j] = x1;
;                         if (i < 2) g2[j] = (i == 1) ? x1 : x0; }
;                     finish(g0, g1, g2, w0, w1, w2, bb, acc[0][bj][m][hv], rs8[0][m], H + (size_t)row * 2816 + col); }
.LBB0_1007:
	v_readlane_b32 s0, v240, 29
	v_mov_b32_e32 v1, v218
	v_mov_b32_e32 v132, v219
	s_add_i32 s2, s2, s0
	v_readlane_b32 s0, v240, 31
	v_add_u32_e32 v210, s2, v1
	v_ashrrev_i32_e32 v211, 31, v210
	v_lshl_add_u64 v[2:3], v[210:211], 2, s[12:13]
	global_load_dword v2, v[2:3], off
	s_waitcnt lgkmcnt(0)
	v_add_u32_e32 v194, 16, v210
	v_ashrrev_i32_e32 v195, 31, v194
	v_add_u32_e32 v192, 32, v210
	v_ashrrev_i32_e32 v193, 31, v192
	v_add_u32_e32 v190, 48, v210
	v_ashrrev_i32_e32 v191, 31, v190
	s_cmpk_lt_i32 s7, 0x80
	s_waitcnt vmcnt(0)
	v_fmamk_f32 v2, v2, 0x3a800000, v224
	v_cmp_gt_f32_e32 vcc, s5, v2
	v_mul_f32_e32 v3, 0x4b800000, v2
	s_nop 0
	v_cndmask_b32_e32 v2, v2, v3, vcc
	v_rsq_f32_e32 v2, v2
	s_nop 0
	v_mul_f32_e32 v3, 0x45800000, v2
	v_cndmask_b32_e32 v188, v2, v3, vcc
	v_lshl_add_u64 v[2:3], v[194:195], 2, s[12:13]
	global_load_dword v2, v[2:3], off
	s_waitcnt vmcnt(0)
	v_fmamk_f32 v2, v2, 0x3a800000, v224
	v_cmp_gt_f32_e32 vcc, s5, v2
	v_mul_f32_e32 v3, 0x4b800000, v2
	s_nop 0
	v_cndmask_b32_e32 v2, v2, v3, vcc
	v_rsq_f32_e32 v2, v2
	s_nop 0
	v_mul_f32_e32 v3, 0x45800000, v2
	v_cndmask_b32_e32 v186, v2, v3, vcc
	v_lshl_add_u64 v[2:3], v[192:193], 2, s[12:13]
	global_load_dword v2, v[2:3], off
	s_waitcnt vmcnt(0)
	v_fmamk_f32 v2, v2, 0x3a800000, v224
	v_cmp_gt_f32_e32 vcc, s5, v2
	v_mul_f32_e32 v3, 0x4b800000, v2
	s_nop 0
	v_cndmask_b32_e32 v2, v2, v3, vcc
	v_rsq_f32_e32 v2, v2
	s_nop 0
	v_mul_f32_e32 v3, 0x45800000, v2
	v_cndmask_b32_e32 v184, v2, v3, vcc
	v_lshl_add_u64 v[2:3], v[190:191], 2, s[12:13]
	global_load_dword v2, v[2:3], off
	s_waitcnt vmcnt(0)
	v_fmamk_f32 v2, v2, 0x3a800000, v224
	v_cmp_gt_f32_e32 vcc, s5, v2
	v_mul_f32_e32 v3, 0x4b800000, v2
	s_nop 0
	v_cndmask_b32_e32 v2, v2, v3, vcc
	v_rsq_f32_e32 v2, v2
	s_nop 0
	v_mul_f32_e32 v3, 0x45800000, v2
	v_cndmask_b32_e32 v2, v2, v3, vcc
	v_lshl_add_u32 v3, v132, 3, s0
	s_mov_b64 s[0:1], -1
	s_cbranch_scc1 .LBB0_1009
	v_lshl_add_u32 v150, s70, 8, v3
	v_ashrrev_i32_e32 v151, 31, v150
	v_readlane_b32 s68, v240, 12
	v_lshlrev_b64 v[160:161], 1, v[150:151]
	v_readlane_b32 s69, v240, 13
	v_add_u32_e32 v134, 0xffff8000, v210
	s_mov_b64 s[86:87], s[54:55]
	v_lshl_add_u64 v[162:163], s[68:69], 0, v[160:161]
	v_mad_i64_i32 v[132:133], s[0:1], v210, s91, v[162:163]
	global_load_dwordx2 v[154:155], v[132:133], off
	v_lshlrev_b64 v[132:133], 2, v[150:151]
	v_lshl_add_u64 v[156:157], s[82:83], 0, v[132:133]
	v_ashrrev_i32_e32 v151, 3, v134
	v_mad_i64_i32 v[134:135], s[0:1], v151, s45, v[156:157]
	v_readlane_b32 s52, v240, 62
	v_add_co_u32_e32 v136, vcc, s41, v134
	v_readlane_b32 s53, v240, 63
	s_nop 0
	v_addc_co_u32_e32 v137, vcc, 0, v135, vcc
	global_load_dwordx4 v[170:173], v[134:135], off
	global_load_dwordx4 v[174:177], v[136:137], off offset:3072
	v_readlane_b32 s54, v239, 0
	v_readlane_b32 s55, v239, 1
	v_readlane_b32 s66, v239, 12
	v_readlane_b32 s67, v239, 13
	v_readlane_b32 s52, v240, 19
	v_readlane_b32 s53, v240, 20
	v_lshl_add_u64 v[134:135], s[66:67], 0, v[132:133]
	v_readlane_b32 s54, v240, 21
	v_lshl_add_u64 v[136:137], s[88:89], 0, v[132:133]
	global_load_dwordx4 v[140:143], v[134:135], off
	global_load_dwordx4 v[144:147], v[136:137], off
	v_lshl_add_u64 v[134:135], s[52:53], 0, v[132:133]
	v_readlane_b32 s55, v240, 22
	global_load_dwordx4 v[136:139], v[134:135], off
	v_add_u32_e32 v152, 0xffff8010, v210
	v_lshl_add_u64 v[132:133], s[54:55], 0, v[132:133]
	global_load_dwordx4 v[132:135], v[132:133], off
	v_readlane_b32 s0, v240, 58
	v_readlane_b32 s1, v240, 59
	v_ashrrev_i32_e32 v168, 3, v152
	v_and_b32_e32 v169, 7, v1
	v_mov_b64_e32 v[158:159], s[0:1]
	v_mad_i64_i32 v[180:181], s[0:1], v168, s45, v[156:157]
	v_mad_i64_i32 v[164:165], s[0:1], v194, s91, v[162:163]
	v_mad_i64_i32 v[178:179], s[0:1], v192, s91, v[162:163]
	v_mad_i64_i32 v[162:163], s[0:1], v190, s91, v[162:163]
	v_add_co_u32_e32 v212, vcc, s41, v180
	global_load_dwordx2 v[166:167], v[164:165], off
	s_nop 0
	global_load_dwordx2 v[164:165], v[178:179], off
	s_nop 0
	global_load_dwordx2 v[162:163], v[162:163], off
	v_addc_co_u32_e32 v213, vcc, 0, v181, vcc
	global_load_dwordx4 v[178:181], v[180:181], off
	s_nop 0
	global_load_dwordx4 v[212:215], v[212:213], off offset:3072
	v_mad_i64_i32 v[152:153], s[0:1], v210, s91, v[158:159]
	v_cmp_eq_u32_e32 vcc, 1, v169
	v_cmp_eq_u32_e64 s[0:1], 0, v169
	v_cmp_gt_u32_e64 s[8:9], 2, v169
	v_mov_b64_e32 v[148:149], s[36:37]
	v_lshl_add_u64 v[182:183], v[152:153], 0, v[160:161]
	v_readlane_b32 s64, v239, 10
	v_readlane_b32 s65, v239, 11
	v_readlane_b32 s64, v240, 23
	v_readlane_b32 s65, v240, 24
	v_readlane_b32 s56, v239, 2
	v_readlane_b32 s57, v239, 3
	v_readlane_b32 s58, v239, 4
	v_readlane_b32 s59, v239, 5
	v_readlane_b32 s60, v239, 6
	v_readlane_b32 s61, v239, 7
	v_readlane_b32 s62, v239, 8
	v_readlane_b32 s63, v239, 9
	s_waitcnt vmcnt(11)
	v_mov_b32_dpp v185, v154 row_ror:1 row_mask:0xf bank_mask:0xf bound_ctrl:1
	v_mov_b32_dpp v187, v155 row_ror:1 row_mask:0xf bank_mask:0xf bound_ctrl:1
	v_mov_b32_dpp v189, v154 row_ror:2 row_mask:0xf bank_mask:0xf bound_ctrl:1
	v_mov_b32_dpp v185, v154 row_shr:1 row_mask:0xf bank_mask:0xf
	v_mov_b32_dpp v187, v155 row_shr:1 row_mask:0xf bank_mask:0xf
	v_mov_b32_dpp v189, v154 row_shr:2 row_mask:0xf bank_mask:0xf
	v_mov_b32_dpp v191, v155 row_ror:2 row_mask:0xf bank_mask:0xf bound_ctrl:1
	v_lshlrev_b32_e32 v226, 16, v154
	v_and_b32_e32 v227, 0xffff0000, v154
	v_mov_b32_dpp v191, v155 row_shr:2 row_mask:0xf bank_mask:0xf
	s_waitcnt vmcnt(9)
; __device__ __forceinline__ unsigned cvt_pk_bf16(float lo, float hi) { unsigned r; asm volatile("v_cvt_pk_bf16_f32 %0, %1, %2" : "=v"(r) : "v"(lo), "v"(hi)); return r; }
;     static __device__ __forceinline__ void finish(const float (&g0)[4], const float (&g1)[4], const float (&g2)[4], const float (&w0)[4], const float (&w1)[4], const float (&w2)[4], const float (&bb)[4],
;                                                   const f32x4 v, float rs, bf16_t* dst) {
;         float h[4];
; #pragma unroll
;         for (int j = 0; j < 4; j += 2) {
;             const f32x2 gc = (f32x2){bb[j] + w0[j] * g2[j] + w1[j] * g1[j] + w2[j] * g0[j], bb[j + 1] + w0[j + 1] * g2[j + 1] + w1[j + 1] * g1[j + 1] + w2[j + 1] * g0[j + 1]};
;             const f32x2 ge = gelu_pk(gc); h[j] = ge.x * v[j] * rs; h[j + 1] = ge.y * v[j + 1] * rs; }
;         u32x2 w; w.x = cvt_pk_bf16(h[0], h[1]); w.y = cvt_pk_bf16(h[2], h[3]);
;         *(u32x2*)dst = w;
;     __device__ __forceinline__ void operator()(const f32x4 (&acc)[2][2][4][2], const Unit& u, int wr, int wc, int fr, int fq) const {
;     ...
;                 for (int m = 0; m < 4; ++m) { const int row = row0 + m * 16; gq[m] = *(const u32x2*)(G + (size_t)row * 2816 + col); }
; #pragma unroll
;                 for (int mh = 0; mh < 4; mh += 2) {
;                 f32x4 c0[4], c1[4];
; #pragma unroll
;                 for (int m = mh; m < mh + 2; ++m) { const int row = row0 + m * 16; const float* cx = ctx + (size_t)((row - 32768) >> 3) * 2 * 2816 + col;
;                     c0[m] = *(const f32x4*)cx; c1[m] = *(const f32x4*)(cx + 2816); }
; #pragma unroll
;                 for (int m = mh; m < mh + 2; ++m) { const int row = row0 + m * 16; const u32x2 cur = gq[m];
;                     const u32x2 q1 = dpp_prev<1>(cur, cur), q2 = dpp_prev<2>(cur, cur);
;                     float g0[4], g1[4], g2[4]; unpk4(cur, g0); unpk4(q1, g1); unpk4(q2, g2);
; #pragma unroll
;                     for (int j = 0; j < 4; ++j) { const float x1 = c1[m][j], x0 = c0[m][j];
;                         if (i < 1) g1[j] = x1;
;                         if (i < 2) g2[j] = (i == 1) ? x1 : x0; }
;                     finish(g0, g1, g2, w0, w1, w2, bb, acc[0][bj][m][hv], rs8[0][m], H + (size_t)row * 2816 + col); }
	v_cndmask_b32_e32 v154, v170, v174, vcc
	v_cndmask_b32_e32 v193, v171, v175, vcc
	v_cndmask_b32_e32 v195, v172, v176, vcc
	v_cndmask_b32_e32 v211, v173, v177, vcc
	v_lshlrev_b32_e32 v170, 16, v185
	v_and_b32_e32 v171, 0xffff0000, v185
	v_lshlrev_b32_e32 v172, 16, v187
	v_and_b32_e32 v173, 0xffff0000, v187
	v_lshlrev_b32_e32 v185, 16, v189
	v_and_b32_e32 v187, 0xffff0000, v189
	v_cndmask_b32_e64 v173, v173, v177, s[0:1]
	v_cndmask_b32_e64 v172, v172, v176, s[0:1]
	v_cndmask_b32_e64 v177, v187, v193, s[8:9]
	v_cndmask_b32_e64 v176, v185, v154, s[8:9]
	v_lshlrev_b32_e32 v189, 16, v191
	v_and_b32_e32 v191, 0xffff0000, v191
	v_cndmask_b32_e64 v171, v171, v175, s[0:1]
	v_cndmask_b32_e64 v170, v170, v174, s[0:1]
	s_waitcnt vmcnt(7)
	v_pk_fma_f32 v[176:177], v[140:141], v[176:177], v[144:145]
	v_cndmask_b32_e64 v175, v191, v211, s[8:9]
	v_cndmask_b32_e64 v174, v189, v195, s[8:9]
	s_waitcnt vmcnt(6)
	v_pk_fma_f32 v[170:171], v[136:137], v[170:171], v[176:177]
	v_pk_fma_f32 v[174:175], v[142:143], v[174:175], v[146:147]
	s_waitcnt vmcnt(5)
	v_pk_fma_f32 v[170:171], v[132:133], v[226:227], v[170:171]
	v_pk_fma_f32 v[172:173], v[138:139], v[172:173], v[174:175]
	v_pk_mul_f32 v[174:175], v[170:171], s[30:31] op_sel_hi:[1,0]
	v_pk_mul_f32 v[170:171], v[170:171], 0.5 op_sel_hi:[1,0]
	v_med3_f32 v174, v174, s47, v225
	v_med3_f32 v175, v175, s47, v225
	v_pk_mul_f32 v[176:177], v[174:175], v[174:175]
	s_nop 0
	v_pk_fma_f32 v[226:227], v[176:177], s[34:35], v[148:149] op_sel_hi:[1,0,0] neg_lo:[1,0,0] neg_hi:[1,0,0]
	s_nop 0
	v_pk_fma_f32 v[226:227], v[176:177], v[226:227], s[38:39] op_sel_hi:[1,1,0]
	s_nop 0
	v_pk_fma_f32 v[226:227], v[176:177], v[226:227], s[40:41] op_sel_hi:[1,1,0]
	s_nop 0
	v_pk_fma_f32 v[226:227], v[176:177], v[226:227], s[42:43] op_sel_hi:[1,1,0]
	s_nop 0
	v_pk_fma_f32 v[226:227], v[176:177], v[226:227], s[44:45] op_sel_hi:[1,1,0]
	s_nop 0
	v_pk_fma_f32 v[226:227], v[176:177], v[226:227], s[46:47] op_sel_hi:[1,1,0]
	s_nop 0
	v_pk_fma_f32 v[176:177], v[176:177], v[226:227], s[48:49] op_sel_hi:[1,1,0]
	s_nop 0
	v_pk_mul_f32 v[174:175], v[174:175], v[176:177]
	s_nop 0
	v_pk_fma_f32 v[170:171], v[170:171], v[174:175], v[170:171]
	s_nop 0
	v_mul_f32_e32 v154, v128, v170
	v_mul_f32_e32 v169, v188, v154
	v_mul_f32_e32 v154, v129, v171
	v_mul_f32_e32 v176, v188, v154
	v_lshlrev_b32_e32 v154, 16, v155
	v_and_b32_e32 v155, 0xffff0000, v155
	v_pk_fma_f32 v[154:155], v[134:135], v[154:155], v[172:173]
	s_nop 0
	v_pk_mul_f32 v[170:171], v[154:155], s[30:31] op_sel_hi:[1,0]
	v_pk_mul_f32 v[154:155], v[154:155], 0.5 op_sel_hi:[1,0]
	v_med3_f32 v170, v170, s47, v225
	v_med3_f32 v171, v171, s47, v225
	v_pk_mul_f32 v[172:173], v[170:171], v[170:171]
	s_nop 0
	v_pk_fma_f32 v[174:175], v[172:173], s[34:35], v[148:149] op_sel_hi:[1,0,0] neg_lo:[1,0,0] neg_hi:[1,0,0]
	s_nop 0
	v_pk_fma_f32 v[174:175], v[172:173], v[174:175], s[38:39] op_sel_hi:[1,1,0]
	s_nop 0
	v_pk_fma_f32 v[174:175], v[172:173], v[174:175], s[40:41] op_sel_hi:[1,1,0]
	s_nop 0
	v_pk_fma_f32 v[174:175], v[172:173], v[174:175], s[42:43] op_sel_hi:[1,1,0]
	s_nop 0
	v_pk_fma_f32 v[174:175], v[172:173], v[174:175], s[44:45] op_sel_hi:[1,1,0]
	s_nop 0
	v_pk_fma_f32 v[174:175], v[172:173], v[174:175], s[46:47] op_sel_hi:[1,1,0]
	s_nop 0
	v_pk_fma_f32 v[172:173], v[172:173], v[174:175], s[48:49] op_sel_hi:[1,1,0]
	s_nop 0
	v_pk_mul_f32 v[170:171], v[170:171], v[172:173]
	s_nop 0
	v_pk_fma_f32 v[154:155], v[154:155], v[170:171], v[154:155]
	s_nop 0
	v_mul_f32_e32 v154, v130, v154
	v_mul_f32_e32 v170, v188, v154
	v_mul_f32_e32 v154, v131, v155
	v_mul_f32_e32 v155, v188, v154
	v_cvt_pk_bf16_f32 v154, v169, v176
	v_cvt_pk_bf16_f32 v155, v170, v155
	global_store_dwordx2 v[182:183], v[154:155], off sc1
	s_waitcnt vmcnt(5)
	v_mov_b32_dpp v169, v166 row_ror:2 row_mask:0xf bank_mask:0xf bound_ctrl:1
	v_mov_b32_dpp v154, v166 row_ror:1 row_mask:0xf bank_mask:0xf bound_ctrl:1
	v_mov_b32_dpp v155, v167 row_ror:1 row_mask:0xf bank_mask:0xf bound_ctrl:1
	v_mov_b32_dpp v170, v167 row_ror:2 row_mask:0xf bank_mask:0xf bound_ctrl:1
	v_mov_b32_dpp v154, v166 row_shr:1 row_mask:0xf bank_mask:0xf
	v_mov_b32_dpp v155, v167 row_shr:1 row_mask:0xf bank_mask:0xf
	v_mov_b32_dpp v169, v166 row_shr:2 row_mask:0xf bank_mask:0xf
	v_mov_b32_dpp v170, v167 row_shr:2 row_mask:0xf bank_mask:0xf
	v_lshlrev_b32_e32 v172, 16, v154
	v_and_b32_e32 v154, 0xffff0000, v154
	v_lshlrev_b32_e32 v174, 16, v155
	v_and_b32_e32 v155, 0xffff0000, v155
	v_lshlrev_b32_e32 v176, 16, v169
	v_and_b32_e32 v169, 0xffff0000, v169
	v_lshlrev_b32_e32 v177, 16, v170
	v_and_b32_e32 v175, 0xffff0000, v170
	s_waitcnt vmcnt(1)
; __device__ __forceinline__ unsigned cvt_pk_bf16(float lo, float hi) { unsigned r; asm volatile("v_cvt_pk_bf16_f32 %0, %1, %2" : "=v"(r) : "v"(lo), "v"(hi)); return r; }
;     static __device__ __forceinline__ void finish(const float (&g0)[4], const float (&g1)[4], const float (&g2)[4], const float (&w0)[4], const float (&w1)[4], const float (&w2)[4], const float (&bb)[4],
;                                                   const f32x4 v, float rs, bf16_t* dst) {
;         float h[4];
; #pragma unroll
;         for (int j = 0; j < 4; j += 2) {
;             const f32x2 gc = (f32x2){bb[j] + w0[j] * g2[j] + w1[j] * g1[j] + w2[j] * g0[j], bb[j + 1] + w0[j + 1] * g2[j + 1] + w1[j + 1] * g1[j + 1] + w2[j + 1] * g0[j + 1]};
;             const f32x2 ge = gelu_pk(gc); h[j] = ge.x * v[j] * rs; h[j + 1] = ge.y * v[j + 1] * rs; }
;         u32x2 w; w.x = cvt_pk_bf16(h[0], h[1]); w.y = cvt_pk_bf16(h[2], h[3]);
;         *(u32x2*)dst = w;
;     __device__ __forceinline__ void operator()(const f32x4 (&acc)[2][2][4][2], const Unit& u, int wr, int wc, int fr, int fq) const {
;     ...
;                 for (int m = 0; m < 4; ++m) { const int row = row0 + m * 16; gq[m] = *(const u32x2*)(G + (size_t)row * 2816 + col); }
; #pragma unroll
;                 for (int mh = 0; mh < 4; mh += 2) {
;                 f32x4 c0[4], c1[4];
; #pragma unroll
;                 for (int m = mh; m < mh + 2; ++m) { const int row = row0 + m * 16; const float* cx = ctx + (size_t)((row - 32768) >> 3) * 2 * 2816 + col;
;                     c0[m] = *(const f32x4*)cx; c1[m] = *(const f32x4*)(cx + 2816); }
; #pragma unroll
;                 for (int m = mh; m < mh + 2; ++m) { const int row = row0 + m * 16; const u32x2 cur = gq[m];
;                     const u32x2 q1 = dpp_prev<1>(cur, cur), q2 = dpp_prev<2>(cur, cur);
;                     float g0[4], g1[4], g2[4]; unpk4(cur, g0); unpk4(q1, g1); unpk4(q2, g2);
; #pragma unroll
;                     for (int j = 0; j < 4; ++j) { const float x1 = c1[m][j], x0 = c0[m][j];
;                         if (i < 1) g1[j] = x1;
;                         if (i < 2) g2[j] = (i == 1) ? x1 : x0; }
;                     finish(g0, g1, g2, w0, w1, w2, bb, acc[0][bj][m][hv], rs8[0][m], H + (size_t)row * 2816 + col); }
	v_cndmask_b32_e64 v171, v154, v213, s[0:1]
	v_cndmask_b32_e64 v170, v172, v212, s[0:1]
	v_cndmask_b32_e64 v173, v155, v215, s[0:1]
	v_cndmask_b32_e64 v172, v174, v214, s[0:1]
	v_cndmask_b32_e32 v154, v178, v212, vcc
	v_cndmask_b32_e32 v155, v179, v213, vcc
	v_cndmask_b32_e32 v174, v180, v214, vcc
	v_cndmask_b32_e64 v174, v177, v174, s[8:9]
	v_cndmask_b32_e64 v177, v169, v155, s[8:9]
	v_cndmask_b32_e64 v176, v176, v154, s[8:9]
	v_cndmask_b32_e32 v178, v181, v215, vcc
	v_pk_fma_f32 v[176:177], v[140:141], v[176:177], v[144:145]
	v_cndmask_b32_e64 v175, v175, v178, s[8:9]
	v_lshlrev_b32_e32 v180, 16, v166
	v_and_b32_e32 v181, 0xffff0000, v166
	v_pk_fma_f32 v[170:171], v[136:137], v[170:171], v[176:177]
	v_pk_fma_f32 v[174:175], v[142:143], v[174:175], v[146:147]
	v_pk_fma_f32 v[170:171], v[132:133], v[180:181], v[170:171]
	v_pk_fma_f32 v[172:173], v[138:139], v[172:173], v[174:175]
	v_pk_mul_f32 v[174:175], v[170:171], s[30:31] op_sel_hi:[1,0]
	v_pk_mul_f32 v[170:171], v[170:171], 0.5 op_sel_hi:[1,0]
	v_med3_f32 v174, v174, s47, v225
	v_med3_f32 v175, v175, s47, v225
	v_pk_mul_f32 v[176:177], v[174:175], v[174:175]
	v_mad_i64_i32 v[154:155], s[10:11], v194, s91, v[158:159]
	v_pk_fma_f32 v[180:181], v[176:177], s[34:35], v[148:149] op_sel_hi:[1,0,0] neg_lo:[1,0,0] neg_hi:[1,0,0]
	v_lshl_add_u64 v[178:179], v[154:155], 0, v[160:161]
	v_pk_fma_f32 v[180:181], v[176:177], v[180:181], s[38:39] op_sel_hi:[1,1,0]
	s_nop 0
	v_pk_fma_f32 v[180:181], v[176:177], v[180:181], s[40:41] op_sel_hi:[1,1,0]
	s_nop 0
	v_pk_fma_f32 v[180:181], v[176:177], v[180:181], s[42:43] op_sel_hi:[1,1,0]
	s_nop 0
	v_pk_fma_f32 v[180:181], v[176:177], v[180:181], s[44:45] op_sel_hi:[1,1,0]
	s_nop 0
	v_pk_fma_f32 v[180:181], v[176:177], v[180:181], s[46:47] op_sel_hi:[1,1,0]
	s_nop 0
	v_pk_fma_f32 v[176:177], v[176:177], v[180:181], s[48:49] op_sel_hi:[1,1,0]
	s_nop 0
	v_pk_mul_f32 v[174:175], v[174:175], v[176:177]
	s_nop 0
	v_pk_fma_f32 v[170:171], v[170:171], v[174:175], v[170:171]
	s_nop 0
	v_mul_f32_e32 v166, v120, v170
	v_mul_f32_e32 v169, v186, v166
	v_mul_f32_e32 v166, v121, v171
	v_mul_f32_e32 v176, v186, v166
	v_lshlrev_b32_e32 v166, 16, v167
	v_and_b32_e32 v167, 0xffff0000, v167
	v_pk_fma_f32 v[166:167], v[134:135], v[166:167], v[172:173]
	s_nop 0
	v_pk_mul_f32 v[170:171], v[166:167], s[30:31] op_sel_hi:[1,0]
	v_pk_mul_f32 v[166:167], v[166:167], 0.5 op_sel_hi:[1,0]
	v_med3_f32 v170, v170, s47, v225
	v_med3_f32 v171, v171, s47, v225
	v_pk_mul_f32 v[172:173], v[170:171], v[170:171]
	s_nop 0
	v_pk_fma_f32 v[174:175], v[172:173], s[34:35], v[148:149] op_sel_hi:[1,0,0] neg_lo:[1,0,0] neg_hi:[1,0,0]
	s_nop 0
	v_pk_fma_f32 v[174:175], v[172:173], v[174:175], s[38:39] op_sel_hi:[1,1,0]
	s_nop 0
	v_pk_fma_f32 v[174:175], v[172:173], v[174:175], s[40:41] op_sel_hi:[1,1,0]
	s_nop 0
	v_pk_fma_f32 v[174:175], v[172:173], v[174:175], s[42:43] op_sel_hi:[1,1,0]
	s_nop 0
	v_pk_fma_f32 v[174:175], v[172:173], v[174:175], s[44:45] op_sel_hi:[1,1,0]
	s_nop 0
	v_pk_fma_f32 v[174:175], v[172:173], v[174:175], s[46:47] op_sel_hi:[1,1,0]
	s_nop 0
	v_pk_fma_f32 v[172:173], v[172:173], v[174:175], s[48:49] op_sel_hi:[1,1,0]
	s_nop 0
	v_pk_mul_f32 v[170:171], v[170:171], v[172:173]
	s_nop 0
	v_pk_fma_f32 v[166:167], v[166:167], v[170:171], v[166:167]
	s_nop 0
	v_mul_f32_e32 v166, v122, v166
	v_mul_f32_e32 v170, v186, v166
	v_mul_f32_e32 v166, v123, v167
	v_mul_f32_e32 v167, v186, v166
	v_cvt_pk_bf16_f32 v166, v169, v176
	v_cvt_pk_bf16_f32 v167, v170, v167
	global_store_dwordx2 v[178:179], v[166:167], off sc1
	v_add_u32_e32 v166, 0xffff8020, v210
	v_ashrrev_i32_e32 v166, 3, v166
	v_mad_i64_i32 v[174:175], s[10:11], v166, s45, v[156:157]
	v_add_co_u32_e64 v170, s[10:11], s41, v174
	v_add_u32_e32 v167, 0xffff8030, v210
	s_nop 0
	v_addc_co_u32_e64 v171, s[10:11], 0, v175, s[10:11]
	global_load_dwordx4 v[170:173], v[170:171], off offset:3072
	s_nop 0
	global_load_dwordx4 v[174:177], v[174:175], off
	v_ashrrev_i32_e32 v167, 3, v167
	v_mad_i64_i32 v[156:157], s[10:11], v167, s45, v[156:157]
	v_add_co_u32_e64 v182, s[10:11], s41, v156
	v_mov_b32_dpp v169, v164 row_ror:2 row_mask:0xf bank_mask:0xf bound_ctrl:1
	s_nop 0
	v_addc_co_u32_e64 v183, s[10:11], 0, v157, s[10:11]
	global_load_dwordx4 v[178:181], v[156:157], off
	global_load_dwordx4 v[212:215], v[182:183], off offset:3072
	v_mov_b32_dpp v156, v164 row_ror:1 row_mask:0xf bank_mask:0xf bound_ctrl:1
	v_mov_b32_dpp v157, v165 row_ror:1 row_mask:0xf bank_mask:0xf bound_ctrl:1
	v_mov_b32_dpp v169, v164 row_shr:2 row_mask:0xf bank_mask:0xf
	v_mov_b32_dpp v156, v164 row_shr:1 row_mask:0xf bank_mask:0xf
	v_mov_b32_dpp v157, v165 row_shr:1 row_mask:0xf bank_mask:0xf
	v_mov_b32_dpp v182, v165 row_ror:2 row_mask:0xf bank_mask:0xf bound_ctrl:1
	v_lshlrev_b32_e32 v185, 16, v156
	v_and_b32_e32 v156, 0xffff0000, v156
	v_lshlrev_b32_e32 v187, 16, v157
	v_and_b32_e32 v157, 0xffff0000, v157
	v_mov_b32_dpp v182, v165 row_shr:2 row_mask:0xf bank_mask:0xf
	v_lshlrev_b32_e32 v189, 16, v169
	v_and_b32_e32 v169, 0xffff0000, v169
	v_lshlrev_b32_e32 v191, 16, v182
	v_and_b32_e32 v193, 0xffff0000, v182
	s_waitcnt vmcnt(3)
	v_cndmask_b32_e64 v183, v156, v171, s[0:1]
	v_cndmask_b32_e64 v227, v157, v173, s[0:1]
	s_waitcnt vmcnt(2)
; __device__ __forceinline__ unsigned cvt_pk_bf16(float lo, float hi) { unsigned r; asm volatile("v_cvt_pk_bf16_f32 %0, %1, %2" : "=v"(r) : "v"(lo), "v"(hi)); return r; }
;     static __device__ __forceinline__ void finish(const float (&g0)[4], const float (&g1)[4], const float (&g2)[4], const float (&w0)[4], const float (&w1)[4], const float (&w2)[4], const float (&bb)[4],
;                                                   const f32x4 v, float rs, bf16_t* dst) {
;         float h[4];
; #pragma unroll
;         for (int j = 0; j < 4; j += 2) {
;             const f32x2 gc = (f32x2){bb[j] + w0[j] * g2[j] + w1[j] * g1[j] + w2[j] * g0[j], bb[j + 1] + w0[j + 1] * g2[j + 1] + w1[j + 1] * g1[j + 1] + w2[j + 1] * g0[j + 1]};
;             const f32x2 ge = gelu_pk(gc); h[j] = ge.x * v[j] * rs; h[j + 1] = ge.y * v[j + 1] * rs; }
;         u32x2 w; w.x = cvt_pk_bf16(h[0], h[1]); w.y = cvt_pk_bf16(h[2], h[3]);
;         *(u32x2*)dst = w;
;     __device__ __forceinline__ void operator()(const f32x4 (&acc)[2][2][4][2], const Unit& u, int wr, int wc, int fr, int fq) const {
;     ...
;                 for (int m = 0; m < 4; ++m) { const int row = row0 + m * 16; gq[m] = *(const u32x2*)(G + (size_t)row * 2816 + col); }
; #pragma unroll
;                 for (int mh = 0; mh < 4; mh += 2) {
;                 f32x4 c0[4], c1[4];
; #pragma unroll
;                 for (int m = mh; m < mh + 2; ++m) { const int row = row0 + m * 16; const float* cx = ctx + (size_t)((row - 32768) >> 3) * 2 * 2816 + col;
;                     c0[m] = *(const f32x4*)cx; c1[m] = *(const f32x4*)(cx + 2816); }
; #pragma unroll
;                 for (int m = mh; m < mh + 2; ++m) { const int row = row0 + m * 16; const u32x2 cur = gq[m];
;                     const u32x2 q1 = dpp_prev<1>(cur, cur), q2 = dpp_prev<2>(cur, cur);
;                     float g0[4], g1[4], g2[4]; unpk4(cur, g0); unpk4(q1, g1); unpk4(q2, g2);
; #pragma unroll
;                     for (int j = 0; j < 4; ++j) { const float x1 = c1[m][j], x0 = c0[m][j];
;                         if (i < 1) g1[j] = x1;
;                         if (i < 2) g2[j] = (i == 1) ? x1 : x0; }
;                     finish(g0, g1, g2, w0, w1, w2, bb, acc[0][bj][m][hv], rs8[0][m], H + (size_t)row * 2816 + col); }
	v_cndmask_b32_e32 v156, v174, v170, vcc
	v_cndmask_b32_e32 v157, v175, v171, vcc
	v_cndmask_b32_e64 v182, v185, v170, s[0:1]
	v_cndmask_b32_e64 v226, v187, v172, s[0:1]
	v_cndmask_b32_e32 v170, v176, v172, vcc
	v_cndmask_b32_e32 v171, v177, v173, vcc
	v_cndmask_b32_e64 v173, v169, v157, s[8:9]
	v_cndmask_b32_e64 v172, v189, v156, s[8:9]
	v_pk_fma_f32 v[172:173], v[140:141], v[172:173], v[144:145]
	v_lshlrev_b32_e32 v176, 16, v164
	v_and_b32_e32 v177, 0xffff0000, v164
	v_pk_fma_f32 v[172:173], v[136:137], v[182:183], v[172:173]
	v_cndmask_b32_e64 v171, v193, v171, s[8:9]
	v_pk_fma_f32 v[172:173], v[132:133], v[176:177], v[172:173]
	v_cndmask_b32_e64 v170, v191, v170, s[8:9]
	v_pk_mul_f32 v[176:177], v[172:173], s[30:31] op_sel_hi:[1,0]
	v_pk_fma_f32 v[170:171], v[142:143], v[170:171], v[146:147]
	v_med3_f32 v176, v176, s47, v225
	v_med3_f32 v177, v177, s47, v225
	v_pk_mul_f32 v[182:183], v[176:177], v[176:177]
	v_pk_fma_f32 v[170:171], v[138:139], v[226:227], v[170:171]
	v_pk_fma_f32 v[226:227], v[182:183], s[34:35], v[148:149] op_sel_hi:[1,0,0] neg_lo:[1,0,0] neg_hi:[1,0,0]
	v_pk_mul_f32 v[172:173], v[172:173], 0.5 op_sel_hi:[1,0]
	v_pk_fma_f32 v[226:227], v[182:183], v[226:227], s[38:39] op_sel_hi:[1,1,0]
	v_mad_i64_i32 v[156:157], s[10:11], v192, s91, v[158:159]
	v_pk_fma_f32 v[226:227], v[182:183], v[226:227], s[40:41] op_sel_hi:[1,1,0]
	v_lshl_add_u64 v[174:175], v[156:157], 0, v[160:161]
	v_pk_fma_f32 v[226:227], v[182:183], v[226:227], s[42:43] op_sel_hi:[1,1,0]
	v_mad_i64_i32 v[158:159], s[10:11], v190, s91, v[158:159]
	v_pk_fma_f32 v[226:227], v[182:183], v[226:227], s[44:45] op_sel_hi:[1,1,0]
	v_lshl_add_u64 v[160:161], v[158:159], 0, v[160:161]
	v_pk_fma_f32 v[226:227], v[182:183], v[226:227], s[46:47] op_sel_hi:[1,1,0]
	s_nop 0
	v_pk_fma_f32 v[182:183], v[182:183], v[226:227], s[48:49] op_sel_hi:[1,1,0]
	s_nop 0
	v_pk_mul_f32 v[176:177], v[176:177], v[182:183]
	s_nop 0
	v_pk_fma_f32 v[172:173], v[172:173], v[176:177], v[172:173]
	s_nop 0
	v_mul_f32_e32 v164, v112, v172
	v_mul_f32_e32 v169, v184, v164
	v_mul_f32_e32 v164, v113, v173
	v_mul_f32_e32 v182, v184, v164
	v_lshlrev_b32_e32 v164, 16, v165
	v_and_b32_e32 v165, 0xffff0000, v165
	v_pk_fma_f32 v[164:165], v[134:135], v[164:165], v[170:171]
	s_nop 0
	v_pk_mul_f32 v[170:171], v[164:165], s[30:31] op_sel_hi:[1,0]
	v_pk_mul_f32 v[164:165], v[164:165], 0.5 op_sel_hi:[1,0]
	v_med3_f32 v170, v170, s47, v225
	v_med3_f32 v171, v171, s47, v225
	v_pk_mul_f32 v[172:173], v[170:171], v[170:171]
	s_nop 0
	v_pk_fma_f32 v[176:177], v[172:173], s[34:35], v[148:149] op_sel_hi:[1,0,0] neg_lo:[1,0,0] neg_hi:[1,0,0]
	s_nop 0
	v_pk_fma_f32 v[176:177], v[172:173], v[176:177], s[38:39] op_sel_hi:[1,1,0]
	s_nop 0
	v_pk_fma_f32 v[176:177], v[172:173], v[176:177], s[40:41] op_sel_hi:[1,1,0]
	s_nop 0
	v_pk_fma_f32 v[176:177], v[172:173], v[176:177], s[42:43] op_sel_hi:[1,1,0]
	s_nop 0
	v_pk_fma_f32 v[176:177], v[172:173], v[176:177], s[44:45] op_sel_hi:[1,1,0]
	s_nop 0
	v_pk_fma_f32 v[176:177], v[172:173], v[176:177], s[46:47] op_sel_hi:[1,1,0]
	s_nop 0
	v_pk_fma_f32 v[172:173], v[172:173], v[176:177], s[48:49] op_sel_hi:[1,1,0]
	s_waitcnt vmcnt(0)
	v_cndmask_b32_e32 v177, v178, v212, vcc
	v_pk_mul_f32 v[170:171], v[170:171], v[172:173]
	v_cndmask_b32_e32 v178, v179, v213, vcc
	v_pk_fma_f32 v[164:165], v[164:165], v[170:171], v[164:165]
	s_nop 0
	v_mul_f32_e32 v164, v114, v164
	v_mul_f32_e32 v170, v184, v164
	v_mul_f32_e32 v164, v115, v165
	v_mul_f32_e32 v165, v184, v164
	v_cvt_pk_bf16_f32 v164, v169, v182
	v_cvt_pk_bf16_f32 v165, v170, v165
	global_store_dwordx2 v[174:175], v[164:165], off sc1
	v_mov_b32_dpp v169, v162 row_ror:2 row_mask:0xf bank_mask:0xf bound_ctrl:1
	v_mov_b32_dpp v165, v163 row_ror:1 row_mask:0xf bank_mask:0xf bound_ctrl:1
	v_mov_b32_dpp v170, v163 row_ror:2 row_mask:0xf bank_mask:0xf bound_ctrl:1
	v_mov_b32_dpp v164, v162 row_ror:1 row_mask:0xf bank_mask:0xf bound_ctrl:1
	v_mov_b32_dpp v165, v163 row_shr:1 row_mask:0xf bank_mask:0xf
	v_mov_b32_dpp v169, v162 row_shr:2 row_mask:0xf bank_mask:0xf
	v_mov_b32_dpp v170, v163 row_shr:2 row_mask:0xf bank_mask:0xf
	v_lshlrev_b32_e32 v172, 16, v165
	v_mov_b32_dpp v164, v162 row_shr:1 row_mask:0xf bank_mask:0xf
	v_lshlrev_b32_e32 v174, 16, v169
	v_and_b32_e32 v169, 0xffff0000, v169
	v_lshlrev_b32_e32 v175, 16, v170
	v_and_b32_e32 v176, 0xffff0000, v170
	v_cndmask_b32_e64 v170, v172, v214, s[0:1]
	v_cndmask_b32_e32 v172, v180, v214, vcc
	v_lshlrev_b32_e32 v171, 16, v164
	v_and_b32_e32 v164, 0xffff0000, v164
	v_and_b32_e32 v173, 0xffff0000, v165
	v_cndmask_b32_e64 v172, v175, v172, s[8:9]
	v_cndmask_b32_e64 v175, v169, v178, s[8:9]
	v_cndmask_b32_e64 v174, v174, v177, s[8:9]
	v_cndmask_b32_e64 v165, v164, v213, s[0:1]
	v_cndmask_b32_e64 v164, v171, v212, s[0:1]
	v_cndmask_b32_e64 v171, v173, v215, s[0:1]
	v_cndmask_b32_e32 v173, v181, v215, vcc
	v_pk_fma_f32 v[140:141], v[140:141], v[174:175], v[144:145]
	v_cndmask_b32_e64 v173, v176, v173, s[8:9]
	v_lshlrev_b32_e32 v176, 16, v162
	v_and_b32_e32 v177, 0xffff0000, v162
	v_pk_fma_f32 v[136:137], v[136:137], v[164:165], v[140:141]
	v_pk_fma_f32 v[142:143], v[142:143], v[172:173], v[146:147]
	v_pk_fma_f32 v[132:133], v[132:133], v[176:177], v[136:137]
	v_pk_fma_f32 v[138:139], v[138:139], v[170:171], v[142:143]
	v_pk_mul_f32 v[136:137], v[132:133], s[30:31] op_sel_hi:[1,0]
	v_pk_mul_f32 v[132:133], v[132:133], 0.5 op_sel_hi:[1,0]
	v_med3_f32 v136, v136, s47, v225
	v_med3_f32 v137, v137, s47, v225
	v_pk_mul_f32 v[140:141], v[136:137], v[136:137]
	s_nop 0
	v_pk_fma_f32 v[142:143], v[140:141], s[34:35], v[148:149] op_sel_hi:[1,0,0] neg_lo:[1,0,0] neg_hi:[1,0,0]
	s_nop 0
; __device__ __forceinline__ unsigned cvt_pk_bf16(float lo, float hi) { unsigned r; asm volatile("v_cvt_pk_bf16_f32 %0, %1, %2" : "=v"(r) : "v"(lo), "v"(hi)); return r; }
;     static __device__ __forceinline__ void finish(const float (&g0)[4], const float (&g1)[4], const float (&g2)[4], const float (&w0)[4], const float (&w1)[4], const float (&w2)[4], const float (&bb)[4],
;                                                   const f32x4 v, float rs, bf16_t* dst) {
;         float h[4];
; #pragma unroll
;         for (int j = 0; j < 4; j += 2) {
;             const f32x2 gc = (f32x2){bb[j] + w0[j] * g2[j] + w1[j] * g1[j] + w2[j] * g0[j], bb[j + 1] + w0[j + 1] * g2[j + 1] + w1[j + 1] * g1[j + 1] + w2[j + 1] * g0[j + 1]};
;             const f32x2 ge = gelu_pk(gc); h[j] = ge.x * v[j] * rs; h[j + 1] = ge.y * v[j + 1] * rs; }
;         u32x2 w; w.x = cvt_pk_bf16(h[0], h[1]); w.y = cvt_pk_bf16(h[2], h[3]);
;         *(u32x2*)dst = w;
;     __device__ __forceinline__ void operator()(const f32x4 (&acc)[2][2][4][2], const Unit& u, int wr, int wc, int fr, int fq) const {
;     ...
;                 for (int m = 0; m < 4; ++m) { const int row = row0 + m * 16; gq[m] = *(const u32x2*)(G + (size_t)row * 2816 + col); }
; #pragma unroll
;                 for (int mh = 0; mh < 4; mh += 2) {
;                 f32x4 c0[4], c1[4];
; #pragma unroll
;                 for (int m = mh; m < mh + 2; ++m) { const int row = row0 + m * 16; const float* cx = ctx + (size_t)((row - 32768) >> 3) * 2 * 2816 + col;
;                     c0[m] = *(const f32x4*)cx; c1[m] = *(const f32x4*)(cx + 2816); }
; #pragma unroll
;                 for (int m = mh; m < mh + 2; ++m) { const int row = row0 + m * 16; const u32x2 cur = gq[m];
;                     const u32x2 q1 = dpp_prev<1>(cur, cur), q2 = dpp_prev<2>(cur, cur);
;                     float g0[4], g1[4], g2[4]; unpk4(cur, g0); unpk4(q1, g1); unpk4(q2, g2);
; #pragma unroll
;                     for (int j = 0; j < 4; ++j) { const float x1 = c1[m][j], x0 = c0[m][j];
;                         if (i < 1) g1[j] = x1;
;                         if (i < 2) g2[j] = (i == 1) ? x1 : x0; }
;                     finish(g0, g1, g2, w0, w1, w2, bb, acc[0][bj][m][hv], rs8[0][m], H + (size_t)row * 2816 + col); }
	v_pk_fma_f32 v[142:143], v[140:141], v[142:143], s[38:39] op_sel_hi:[1,1,0]
	s_nop 0
	v_pk_fma_f32 v[142:143], v[140:141], v[142:143], s[40:41] op_sel_hi:[1,1,0]
	s_nop 0
	v_pk_fma_f32 v[142:143], v[140:141], v[142:143], s[42:43] op_sel_hi:[1,1,0]
	s_nop 0
	v_pk_fma_f32 v[142:143], v[140:141], v[142:143], s[44:45] op_sel_hi:[1,1,0]
	s_nop 0
	v_pk_fma_f32 v[142:143], v[140:141], v[142:143], s[46:47] op_sel_hi:[1,1,0]
	s_nop 0
	v_pk_fma_f32 v[140:141], v[140:141], v[142:143], s[48:49] op_sel_hi:[1,1,0]
	s_nop 0
	v_pk_mul_f32 v[136:137], v[136:137], v[140:141]
	s_nop 0
	v_pk_fma_f32 v[132:133], v[132:133], v[136:137], v[132:133]
	s_nop 0
	v_mul_f32_e32 v132, v104, v132
	v_mul_f32_e32 v140, v2, v132
	v_mul_f32_e32 v132, v105, v133
	v_mul_f32_e32 v141, v2, v132
	v_lshlrev_b32_e32 v132, 16, v163
	v_and_b32_e32 v133, 0xffff0000, v163
	v_pk_fma_f32 v[132:133], v[134:135], v[132:133], v[138:139]
	s_nop 0
	v_pk_mul_f32 v[134:135], v[132:133], s[30:31] op_sel_hi:[1,0]
	v_pk_mul_f32 v[132:133], v[132:133], 0.5 op_sel_hi:[1,0]
	v_med3_f32 v134, v134, s47, v225
	v_med3_f32 v135, v135, s47, v225
	v_pk_mul_f32 v[136:137], v[134:135], v[134:135]
	s_nop 0
	v_pk_fma_f32 v[138:139], v[136:137], s[34:35], v[148:149] op_sel_hi:[1,0,0] neg_lo:[1,0,0] neg_hi:[1,0,0]
	s_nop 0
	v_pk_fma_f32 v[138:139], v[136:137], v[138:139], s[38:39] op_sel_hi:[1,1,0]
	s_nop 0
	v_pk_fma_f32 v[138:139], v[136:137], v[138:139], s[40:41] op_sel_hi:[1,1,0]
	s_nop 0
	v_pk_fma_f32 v[138:139], v[136:137], v[138:139], s[42:43] op_sel_hi:[1,1,0]
	s_nop 0
	v_pk_fma_f32 v[138:139], v[136:137], v[138:139], s[44:45] op_sel_hi:[1,1,0]
	s_nop 0
	v_pk_fma_f32 v[138:139], v[136:137], v[138:139], s[46:47] op_sel_hi:[1,1,0]
	s_nop 0
	v_pk_fma_f32 v[136:137], v[136:137], v[138:139], s[48:49] op_sel_hi:[1,1,0]
	s_nop 0
	v_pk_mul_f32 v[134:135], v[134:135], v[136:137]
	s_nop 0
	v_pk_fma_f32 v[132:133], v[132:133], v[134:135], v[132:133]
	s_nop 0
	v_mul_f32_e32 v132, v106, v132
	v_mul_f32_e32 v134, v2, v132
	v_mul_f32_e32 v132, v107, v133
	v_mul_f32_e32 v133, v2, v132
	v_cvt_pk_bf16_f32 v132, v140, v141
	v_cvt_pk_bf16_f32 v133, v134, v133
	global_store_dwordx2 v[160:161], v[132:133], off sc1
	v_add_u32_e32 v132, 4, v150
	v_ashrrev_i32_e32 v133, 31, v132
	v_lshlrev_b64 v[162:163], 1, v[132:133]
	v_lshl_add_u64 v[160:161], s[68:69], 0, v[162:163]
	v_lshlrev_b64 v[132:133], 2, v[132:133]
	v_mad_i64_i32 v[134:135], s[10:11], v210, s91, v[160:161]
	v_lshl_add_u64 v[226:227], s[82:83], 0, v[132:133]
	global_load_dwordx2 v[182:183], v[134:135], off
	v_mad_i64_i32 v[134:135], s[10:11], v151, s45, v[226:227]
	v_add_co_u32_e64 v136, s[10:11], s41, v134
	s_waitcnt vmcnt(0)
	v_mov_b32_dpp v169, v182 row_ror:1 row_mask:0xf bank_mask:0xf bound_ctrl:1
	v_addc_co_u32_e64 v137, s[10:11], 0, v135, s[10:11]
	global_load_dwordx4 v[170:173], v[136:137], off offset:3072
	global_load_dwordx4 v[174:177], v[134:135], off
	v_lshl_add_u64 v[134:135], s[66:67], 0, v[132:133]
	global_load_dwordx4 v[140:143], v[134:135], off
	v_lshl_add_u64 v[134:135], s[88:89], 0, v[132:133]
	global_load_dwordx4 v[144:147], v[134:135], off
	v_lshl_add_u64 v[134:135], s[52:53], 0, v[132:133]
	global_load_dwordx4 v[136:139], v[134:135], off
	v_lshl_add_u64 v[132:133], s[54:55], 0, v[132:133]
	global_load_dwordx4 v[132:135], v[132:133], off
	v_mad_i64_i32 v[164:165], s[10:11], v194, s91, v[160:161]
	v_mad_i64_i32 v[178:179], s[10:11], v192, s91, v[160:161]
	v_mad_i64_i32 v[160:161], s[10:11], v190, s91, v[160:161]
	global_load_dwordx2 v[228:229], v[164:165], off
	s_nop 0
	global_load_dwordx2 v[164:165], v[178:179], off
	s_nop 0
	global_load_dwordx2 v[160:161], v[160:161], off
	v_mad_i64_i32 v[178:179], s[10:11], v168, s45, v[226:227]
	v_add_co_u32_e64 v212, s[10:11], s41, v178
	v_mov_b32_dpp v169, v182 row_shr:1 row_mask:0xf bank_mask:0xf
	s_nop 0
	v_addc_co_u32_e64 v213, s[10:11], 0, v179, s[10:11]
	global_load_dwordx4 v[178:181], v[178:179], off
	s_nop 0
	global_load_dwordx4 v[212:215], v[212:213], off offset:3072
	v_mov_b32_dpp v185, v183 row_ror:1 row_mask:0xf bank_mask:0xf bound_ctrl:1
	v_mov_b32_dpp v187, v182 row_ror:2 row_mask:0xf bank_mask:0xf bound_ctrl:1
	v_lshlrev_b32_e32 v191, 16, v169
	v_mov_b32_dpp v185, v183 row_shr:1 row_mask:0xf bank_mask:0xf
	v_mov_b32_dpp v187, v182 row_shr:2 row_mask:0xf bank_mask:0xf
	v_and_b32_e32 v169, 0xffff0000, v169
	v_lshlrev_b32_e32 v193, 16, v185
	v_and_b32_e32 v185, 0xffff0000, v185
	v_lshlrev_b32_e32 v195, 16, v187
	v_and_b32_e32 v187, 0xffff0000, v187
	v_mov_b32_dpp v189, v183 row_ror:2 row_mask:0xf bank_mask:0xf bound_ctrl:1
	s_waitcnt vmcnt(10)
	v_cndmask_b32_e64 v231, v169, v171, s[0:1]
	s_waitcnt vmcnt(9)
	v_cndmask_b32_e32 v169, v174, v170, vcc
	v_cndmask_b32_e32 v174, v175, v171, vcc
	v_cndmask_b32_e64 v230, v191, v170, s[0:1]
	v_cndmask_b32_e64 v233, v185, v173, s[0:1]
	v_cndmask_b32_e64 v232, v193, v172, s[0:1]
	v_cndmask_b32_e32 v170, v176, v172, vcc
	v_cndmask_b32_e32 v171, v177, v173, vcc
	v_cndmask_b32_e64 v173, v187, v174, s[8:9]
	v_cndmask_b32_e64 v172, v195, v169, s[8:9]
	s_waitcnt vmcnt(7)
	v_pk_fma_f32 v[172:173], v[140:141], v[172:173], v[144:145]
	v_lshlrev_b32_e32 v176, 16, v182
	v_and_b32_e32 v177, 0xffff0000, v182
	s_waitcnt vmcnt(6)
	v_pk_fma_f32 v[172:173], v[136:137], v[230:231], v[172:173]
	v_mov_b32_dpp v189, v183 row_shr:2 row_mask:0xf bank_mask:0xf
	s_waitcnt vmcnt(5)
; __device__ __forceinline__ unsigned cvt_pk_bf16(float lo, float hi) { unsigned r; asm volatile("v_cvt_pk_bf16_f32 %0, %1, %2" : "=v"(r) : "v"(lo), "v"(hi)); return r; }
;     static __device__ __forceinline__ void finish(const float (&g0)[4], const float (&g1)[4], const float (&g2)[4], const float (&w0)[4], const float (&w1)[4], const float (&w2)[4], const float (&bb)[4],
;                                                   const f32x4 v, float rs, bf16_t* dst) {
;         float h[4];
; #pragma unroll
;         for (int j = 0; j < 4; j += 2) {
;             const f32x2 gc = (f32x2){bb[j] + w0[j] * g2[j] + w1[j] * g1[j] + w2[j] * g0[j], bb[j + 1] + w0[j + 1] * g2[j + 1] + w1[j + 1] * g1[j + 1] + w2[j + 1] * g0[j + 1]};
;             const f32x2 ge = gelu_pk(gc); h[j] = ge.x * v[j] * rs; h[j + 1] = ge.y * v[j + 1] * rs; }
;         u32x2 w; w.x = cvt_pk_bf16(h[0], h[1]); w.y = cvt_pk_bf16(h[2], h[3]);
;         *(u32x2*)dst = w;
;     __device__ __forceinline__ void operator()(const f32x4 (&acc)[2][2][4][2], const Unit& u, int wr, int wc, int fr, int fq) const {
;     ...
;                 for (int m = 0; m < 4; ++m) { const int row = row0 + m * 16; gq[m] = *(const u32x2*)(G + (size_t)row * 2816 + col); }
; #pragma unroll
;                 for (int mh = 0; mh < 4; mh += 2) {
;                 f32x4 c0[4], c1[4];
; #pragma unroll
;                 for (int m = mh; m < mh + 2; ++m) { const int row = row0 + m * 16; const float* cx = ctx + (size_t)((row - 32768) >> 3) * 2 * 2816 + col;
;                     c0[m] = *(const f32x4*)cx; c1[m] = *(const f32x4*)(cx + 2816); }
; #pragma unroll
;                 for (int m = mh; m < mh + 2; ++m) { const int row = row0 + m * 16; const u32x2 cur = gq[m];
;                     const u32x2 q1 = dpp_prev<1>(cur, cur), q2 = dpp_prev<2>(cur, cur);
;                     float g0[4], g1[4], g2[4]; unpk4(cur, g0); unpk4(q1, g1); unpk4(q2, g2);
; #pragma unroll
;                     for (int j = 0; j < 4; ++j) { const float x1 = c1[m][j], x0 = c0[m][j];
;                         if (i < 1) g1[j] = x1;
;                         if (i < 2) g2[j] = (i == 1) ? x1 : x0; }
;                     finish(g0, g1, g2, w0, w1, w2, bb, acc[0][bj][m][hv], rs8[0][m], H + (size_t)row * 2816 + col); }
	v_pk_fma_f32 v[172:173], v[132:133], v[176:177], v[172:173]
	v_lshlrev_b32_e32 v211, 16, v189
	v_and_b32_e32 v189, 0xffff0000, v189
	v_pk_mul_f32 v[176:177], v[172:173], s[30:31] op_sel_hi:[1,0]
	v_cndmask_b32_e64 v171, v189, v171, s[8:9]
	v_cndmask_b32_e64 v170, v211, v170, s[8:9]
	v_med3_f32 v176, v176, s47, v225
	v_med3_f32 v177, v177, s47, v225
	v_pk_fma_f32 v[170:171], v[142:143], v[170:171], v[146:147]
	v_pk_mul_f32 v[230:231], v[176:177], v[176:177]
	v_pk_fma_f32 v[170:171], v[138:139], v[232:233], v[170:171]
	v_pk_fma_f32 v[232:233], v[230:231], s[34:35], v[148:149] op_sel_hi:[1,0,0] neg_lo:[1,0,0] neg_hi:[1,0,0]
	v_pk_mul_f32 v[172:173], v[172:173], 0.5 op_sel_hi:[1,0]
	v_pk_fma_f32 v[232:233], v[230:231], v[232:233], s[38:39] op_sel_hi:[1,1,0]
	v_lshl_add_u64 v[174:175], v[152:153], 0, v[162:163]
	v_pk_fma_f32 v[232:233], v[230:231], v[232:233], s[40:41] op_sel_hi:[1,1,0]
	s_nop 0
	v_pk_fma_f32 v[232:233], v[230:231], v[232:233], s[42:43] op_sel_hi:[1,1,0]
	s_nop 0
	v_pk_fma_f32 v[232:233], v[230:231], v[232:233], s[44:45] op_sel_hi:[1,1,0]
	s_nop 0
	v_pk_fma_f32 v[232:233], v[230:231], v[232:233], s[46:47] op_sel_hi:[1,1,0]
	s_nop 0
	v_pk_fma_f32 v[230:231], v[230:231], v[232:233], s[48:49] op_sel_hi:[1,1,0]
	s_nop 0
	v_pk_mul_f32 v[176:177], v[176:177], v[230:231]
	s_nop 0
	v_pk_fma_f32 v[172:173], v[172:173], v[176:177], v[172:173]
	s_nop 0
	v_mul_f32_e32 v169, v124, v172
	v_mul_f32_e32 v172, v125, v173
	v_mul_f32_e32 v185, v188, v172
	v_lshlrev_b32_e32 v172, 16, v183
	v_and_b32_e32 v173, 0xffff0000, v183
	v_pk_fma_f32 v[170:171], v[134:135], v[172:173], v[170:171]
	v_mul_f32_e32 v169, v188, v169
	v_pk_mul_f32 v[172:173], v[170:171], s[30:31] op_sel_hi:[1,0]
	v_pk_mul_f32 v[170:171], v[170:171], 0.5 op_sel_hi:[1,0]
	v_med3_f32 v172, v172, s47, v225
	v_med3_f32 v173, v173, s47, v225
	v_pk_mul_f32 v[176:177], v[172:173], v[172:173]
	s_nop 0
	v_pk_fma_f32 v[182:183], v[176:177], s[34:35], v[148:149] op_sel_hi:[1,0,0] neg_lo:[1,0,0] neg_hi:[1,0,0]
	s_nop 0
	v_pk_fma_f32 v[182:183], v[176:177], v[182:183], s[38:39] op_sel_hi:[1,1,0]
	s_nop 0
	v_pk_fma_f32 v[182:183], v[176:177], v[182:183], s[40:41] op_sel_hi:[1,1,0]
	s_nop 0
	v_pk_fma_f32 v[182:183], v[176:177], v[182:183], s[42:43] op_sel_hi:[1,1,0]
	s_nop 0
	v_pk_fma_f32 v[182:183], v[176:177], v[182:183], s[44:45] op_sel_hi:[1,1,0]
	s_nop 0
	v_pk_fma_f32 v[182:183], v[176:177], v[182:183], s[46:47] op_sel_hi:[1,1,0]
	s_nop 0
	v_pk_fma_f32 v[176:177], v[176:177], v[182:183], s[48:49] op_sel_hi:[1,1,0]
	s_nop 0
	v_pk_mul_f32 v[172:173], v[172:173], v[176:177]
	s_nop 0
	v_pk_fma_f32 v[170:171], v[170:171], v[172:173], v[170:171]
	s_nop 0
	v_mul_f32_e32 v170, v126, v170
	v_mul_f32_e32 v172, v188, v170
	v_mul_f32_e32 v170, v127, v171
	v_mul_f32_e32 v171, v188, v170
	v_cvt_pk_bf16_f32 v170, v169, v185
	v_cvt_pk_bf16_f32 v171, v172, v171
	s_waitcnt vmcnt(4)
	v_mov_b32_dpp v169, v228 row_ror:1 row_mask:0xf bank_mask:0xf bound_ctrl:1
	global_store_dwordx2 v[174:175], v[170:171], off sc1
	v_mov_b32_dpp v171, v228 row_ror:2 row_mask:0xf bank_mask:0xf bound_ctrl:1
	v_mov_b32_dpp v169, v228 row_shr:1 row_mask:0xf bank_mask:0xf
	v_mov_b32_dpp v170, v229 row_ror:1 row_mask:0xf bank_mask:0xf bound_ctrl:1
	v_mov_b32_dpp v171, v228 row_shr:2 row_mask:0xf bank_mask:0xf
	v_lshlrev_b32_e32 v173, 16, v169
	v_and_b32_e32 v169, 0xffff0000, v169
	v_mov_b32_dpp v170, v229 row_shr:1 row_mask:0xf bank_mask:0xf
	v_mov_b32_dpp v172, v229 row_ror:2 row_mask:0xf bank_mask:0xf bound_ctrl:1
	v_lshlrev_b32_e32 v176, 16, v171
	v_and_b32_e32 v177, 0xffff0000, v171
	s_waitcnt vmcnt(1)
	v_cndmask_b32_e64 v171, v169, v213, s[0:1]
	v_cndmask_b32_e32 v169, v178, v212, vcc
	v_cndmask_b32_e32 v178, v179, v213, vcc
	v_mov_b32_dpp v172, v229 row_shr:2 row_mask:0xf bank_mask:0xf
	v_lshlrev_b32_e32 v174, 16, v170
	v_and_b32_e32 v175, 0xffff0000, v170
	v_cndmask_b32_e64 v177, v177, v178, s[8:9]
	v_cndmask_b32_e64 v176, v176, v169, s[8:9]
	v_lshlrev_b32_e32 v182, 16, v172
	v_and_b32_e32 v183, 0xffff0000, v172
	v_cndmask_b32_e64 v170, v173, v212, s[0:1]
	v_cndmask_b32_e64 v173, v175, v215, s[0:1]
	v_cndmask_b32_e64 v172, v174, v214, s[0:1]
	v_cndmask_b32_e32 v174, v180, v214, vcc
	v_cndmask_b32_e32 v175, v181, v215, vcc
	v_pk_fma_f32 v[176:177], v[140:141], v[176:177], v[144:145]
	v_cndmask_b32_e64 v175, v183, v175, s[8:9]
	v_cndmask_b32_e64 v174, v182, v174, s[8:9]
	v_lshlrev_b32_e32 v180, 16, v228
	v_and_b32_e32 v181, 0xffff0000, v228
	v_pk_fma_f32 v[170:171], v[136:137], v[170:171], v[176:177]
	v_pk_fma_f32 v[174:175], v[142:143], v[174:175], v[146:147]
	v_pk_fma_f32 v[170:171], v[132:133], v[180:181], v[170:171]
	v_pk_fma_f32 v[172:173], v[138:139], v[172:173], v[174:175]
	v_pk_mul_f32 v[174:175], v[170:171], s[30:31] op_sel_hi:[1,0]
	v_pk_mul_f32 v[170:171], v[170:171], 0.5 op_sel_hi:[1,0]
	v_med3_f32 v174, v174, s47, v225
	v_med3_f32 v175, v175, s47, v225
	v_pk_mul_f32 v[176:177], v[174:175], v[174:175]
	v_lshl_add_u64 v[178:179], v[154:155], 0, v[162:163]
	v_pk_fma_f32 v[180:181], v[176:177], s[34:35], v[148:149] op_sel_hi:[1,0,0] neg_lo:[1,0,0] neg_hi:[1,0,0]
	v_mov_b32_dpp v185, v165 row_ror:2 row_mask:0xf bank_mask:0xf bound_ctrl:1
	v_pk_fma_f32 v[180:181], v[176:177], v[180:181], s[38:39] op_sel_hi:[1,1,0]
	s_nop 0
	v_pk_fma_f32 v[180:181], v[176:177], v[180:181], s[40:41] op_sel_hi:[1,1,0]
	v_mov_b32_dpp v185, v165 row_shr:2 row_mask:0xf bank_mask:0xf
	v_pk_fma_f32 v[180:181], v[176:177], v[180:181], s[42:43] op_sel_hi:[1,1,0]
	v_lshlrev_b32_e32 v211, 16, v185
	v_pk_fma_f32 v[180:181], v[176:177], v[180:181], s[44:45] op_sel_hi:[1,1,0]
	v_and_b32_e32 v185, 0xffff0000, v185
; __device__ __forceinline__ unsigned cvt_pk_bf16(float lo, float hi) { unsigned r; asm volatile("v_cvt_pk_bf16_f32 %0, %1, %2" : "=v"(r) : "v"(lo), "v"(hi)); return r; }
;     static __device__ __forceinline__ void finish(const float (&g0)[4], const float (&g1)[4], const float (&g2)[4], const float (&w0)[4], const float (&w1)[4], const float (&w2)[4], const float (&bb)[4],
;                                                   const f32x4 v, float rs, bf16_t* dst) {
;         float h[4];
; #pragma unroll
;         for (int j = 0; j < 4; j += 2) {
;             const f32x2 gc = (f32x2){bb[j] + w0[j] * g2[j] + w1[j] * g1[j] + w2[j] * g0[j], bb[j + 1] + w0[j + 1] * g2[j + 1] + w1[j + 1] * g1[j + 1] + w2[j + 1] * g0[j + 1]};
;             const f32x2 ge = gelu_pk(gc); h[j] = ge.x * v[j] * rs; h[j + 1] = ge.y * v[j + 1] * rs; }
;         u32x2 w; w.x = cvt_pk_bf16(h[0], h[1]); w.y = cvt_pk_bf16(h[2], h[3]);
;         *(u32x2*)dst = w;
;     __device__ __forceinline__ void operator()(const f32x4 (&acc)[2][2][4][2], const Unit& u, int wr, int wc, int fr, int fq) const {
;     ...
;                 for (int m = 0; m < 4; ++m) { const int row = row0 + m * 16; gq[m] = *(const u32x2*)(G + (size_t)row * 2816 + col); }
; #pragma unroll
;                 for (int mh = 0; mh < 4; mh += 2) {
;                 f32x4 c0[4], c1[4];
; #pragma unroll
;                 for (int m = mh; m < mh + 2; ++m) { const int row = row0 + m * 16; const float* cx = ctx + (size_t)((row - 32768) >> 3) * 2 * 2816 + col;
;                     c0[m] = *(const f32x4*)cx; c1[m] = *(const f32x4*)(cx + 2816); }
; #pragma unroll
;                 for (int m = mh; m < mh + 2; ++m) { const int row = row0 + m * 16; const u32x2 cur = gq[m];
;                     const u32x2 q1 = dpp_prev<1>(cur, cur), q2 = dpp_prev<2>(cur, cur);
;                     float g0[4], g1[4], g2[4]; unpk4(cur, g0); unpk4(q1, g1); unpk4(q2, g2);
; #pragma unroll
;                     for (int j = 0; j < 4; ++j) { const float x1 = c1[m][j], x0 = c0[m][j];
;                         if (i < 1) g1[j] = x1;
;                         if (i < 2) g2[j] = (i == 1) ? x1 : x0; }
;                     finish(g0, g1, g2, w0, w1, w2, bb, acc[0][bj][m][hv], rs8[0][m], H + (size_t)row * 2816 + col); }
	v_pk_fma_f32 v[180:181], v[176:177], v[180:181], s[46:47] op_sel_hi:[1,1,0]
	s_nop 0
	v_pk_fma_f32 v[176:177], v[176:177], v[180:181], s[48:49] op_sel_hi:[1,1,0]
	s_nop 0
	v_pk_mul_f32 v[174:175], v[174:175], v[176:177]
	s_nop 0
	v_pk_fma_f32 v[170:171], v[170:171], v[174:175], v[170:171]
	s_nop 0
	v_mul_f32_e32 v169, v116, v170
	v_mul_f32_e32 v170, v117, v171
	v_mul_f32_e32 v180, v186, v170
	v_lshlrev_b32_e32 v170, 16, v229
	v_and_b32_e32 v171, 0xffff0000, v229
	v_pk_fma_f32 v[170:171], v[134:135], v[170:171], v[172:173]
	v_mul_f32_e32 v169, v186, v169
	v_pk_mul_f32 v[172:173], v[170:171], s[30:31] op_sel_hi:[1,0]
	v_pk_mul_f32 v[170:171], v[170:171], 0.5 op_sel_hi:[1,0]
	v_med3_f32 v172, v172, s47, v225
	v_med3_f32 v173, v173, s47, v225
	v_pk_mul_f32 v[174:175], v[172:173], v[172:173]
	s_nop 0
	v_pk_fma_f32 v[176:177], v[174:175], s[34:35], v[148:149] op_sel_hi:[1,0,0] neg_lo:[1,0,0] neg_hi:[1,0,0]
	s_nop 0
	v_pk_fma_f32 v[176:177], v[174:175], v[176:177], s[38:39] op_sel_hi:[1,1,0]
	s_nop 0
	v_pk_fma_f32 v[176:177], v[174:175], v[176:177], s[40:41] op_sel_hi:[1,1,0]
	s_nop 0
	v_pk_fma_f32 v[176:177], v[174:175], v[176:177], s[42:43] op_sel_hi:[1,1,0]
	s_nop 0
	v_pk_fma_f32 v[176:177], v[174:175], v[176:177], s[44:45] op_sel_hi:[1,1,0]
	s_nop 0
	v_pk_fma_f32 v[176:177], v[174:175], v[176:177], s[46:47] op_sel_hi:[1,1,0]
	s_nop 0
	v_pk_fma_f32 v[174:175], v[174:175], v[176:177], s[48:49] op_sel_hi:[1,1,0]
	s_nop 0
	v_pk_mul_f32 v[172:173], v[172:173], v[174:175]
	v_mad_i64_i32 v[174:175], s[10:11], v166, s45, v[226:227]
	v_pk_fma_f32 v[170:171], v[170:171], v[172:173], v[170:171]
	s_nop 0
	v_mul_f32_e32 v170, v118, v170
	v_mul_f32_e32 v172, v186, v170
	v_mul_f32_e32 v170, v119, v171
	v_mul_f32_e32 v171, v186, v170
	v_cvt_pk_bf16_f32 v170, v169, v180
	v_cvt_pk_bf16_f32 v171, v172, v171
	global_store_dwordx2 v[178:179], v[170:171], off sc1
	v_add_co_u32_e64 v170, s[10:11], s41, v174
	v_mov_b32_dpp v169, v164 row_ror:1 row_mask:0xf bank_mask:0xf bound_ctrl:1
	s_nop 0
	v_addc_co_u32_e64 v171, s[10:11], 0, v175, s[10:11]
	global_load_dwordx4 v[170:173], v[170:171], off offset:3072
	s_nop 0
	global_load_dwordx4 v[174:177], v[174:175], off
	v_mad_i64_i32 v[178:179], s[10:11], v167, s45, v[226:227]
	v_add_co_u32_e64 v182, s[10:11], s41, v178
	v_mov_b32_dpp v169, v164 row_shr:1 row_mask:0xf bank_mask:0xf
	s_nop 0
	v_addc_co_u32_e64 v183, s[10:11], 0, v179, s[10:11]
	global_load_dwordx4 v[178:181], v[178:179], off
	s_nop 0
	global_load_dwordx4 v[212:215], v[182:183], off offset:3072
	v_mov_b32_dpp v182, v165 row_ror:1 row_mask:0xf bank_mask:0xf bound_ctrl:1
	v_mov_b32_dpp v183, v164 row_ror:2 row_mask:0xf bank_mask:0xf bound_ctrl:1
	v_lshlrev_b32_e32 v187, 16, v169
	v_mov_b32_dpp v182, v165 row_shr:1 row_mask:0xf bank_mask:0xf
	v_mov_b32_dpp v183, v164 row_shr:2 row_mask:0xf bank_mask:0xf
	v_and_b32_e32 v169, 0xffff0000, v169
	v_lshlrev_b32_e32 v189, 16, v182
	v_and_b32_e32 v191, 0xffff0000, v182
	v_lshlrev_b32_e32 v193, 16, v183
	v_and_b32_e32 v195, 0xffff0000, v183
	s_waitcnt vmcnt(3)
	v_cndmask_b32_e64 v183, v169, v171, s[0:1]
	s_waitcnt vmcnt(2)
	v_cndmask_b32_e32 v169, v174, v170, vcc
	v_cndmask_b32_e32 v174, v175, v171, vcc
	v_cndmask_b32_e64 v182, v187, v170, s[0:1]
	v_cndmask_b32_e64 v227, v191, v173, s[0:1]
	v_cndmask_b32_e64 v226, v189, v172, s[0:1]
	v_cndmask_b32_e32 v170, v176, v172, vcc
	v_cndmask_b32_e32 v171, v177, v173, vcc
	v_cndmask_b32_e64 v173, v195, v174, s[8:9]
	v_cndmask_b32_e64 v172, v193, v169, s[8:9]
	v_pk_fma_f32 v[172:173], v[140:141], v[172:173], v[144:145]
	v_lshlrev_b32_e32 v176, 16, v164
	v_and_b32_e32 v177, 0xffff0000, v164
	v_pk_fma_f32 v[172:173], v[136:137], v[182:183], v[172:173]
	v_cndmask_b32_e64 v171, v185, v171, s[8:9]
	v_pk_fma_f32 v[172:173], v[132:133], v[176:177], v[172:173]
	v_cndmask_b32_e64 v170, v211, v170, s[8:9]
	v_pk_mul_f32 v[176:177], v[172:173], s[30:31] op_sel_hi:[1,0]
	v_pk_fma_f32 v[170:171], v[142:143], v[170:171], v[146:147]
	v_med3_f32 v176, v176, s47, v225
	v_med3_f32 v177, v177, s47, v225
	v_pk_mul_f32 v[182:183], v[176:177], v[176:177]
	v_pk_fma_f32 v[170:171], v[138:139], v[226:227], v[170:171]
	v_pk_fma_f32 v[226:227], v[182:183], s[34:35], v[148:149] op_sel_hi:[1,0,0] neg_lo:[1,0,0] neg_hi:[1,0,0]
	v_pk_mul_f32 v[172:173], v[172:173], 0.5 op_sel_hi:[1,0]
	v_pk_fma_f32 v[226:227], v[182:183], v[226:227], s[38:39] op_sel_hi:[1,1,0]
	v_lshl_add_u64 v[174:175], v[156:157], 0, v[162:163]
	v_pk_fma_f32 v[226:227], v[182:183], v[226:227], s[40:41] op_sel_hi:[1,1,0]
	v_lshl_add_u64 v[162:163], v[158:159], 0, v[162:163]
	v_pk_fma_f32 v[226:227], v[182:183], v[226:227], s[42:43] op_sel_hi:[1,1,0]
	s_nop 0
	v_pk_fma_f32 v[226:227], v[182:183], v[226:227], s[44:45] op_sel_hi:[1,1,0]
	s_nop 0
	v_pk_fma_f32 v[226:227], v[182:183], v[226:227], s[46:47] op_sel_hi:[1,1,0]
	s_nop 0
	v_pk_fma_f32 v[182:183], v[182:183], v[226:227], s[48:49] op_sel_hi:[1,1,0]
	s_nop 0
	v_pk_mul_f32 v[176:177], v[176:177], v[182:183]
	s_nop 0
	v_pk_fma_f32 v[172:173], v[172:173], v[176:177], v[172:173]
	s_nop 0
	v_mul_f32_e32 v164, v108, v172
	v_mul_f32_e32 v169, v184, v164
	v_mul_f32_e32 v164, v109, v173
	v_mul_f32_e32 v182, v184, v164
	v_lshlrev_b32_e32 v164, 16, v165
	v_and_b32_e32 v165, 0xffff0000, v165
	v_pk_fma_f32 v[164:165], v[134:135], v[164:165], v[170:171]
	s_nop 0
	v_pk_mul_f32 v[170:171], v[164:165], s[30:31] op_sel_hi:[1,0]
	v_pk_mul_f32 v[164:165], v[164:165], 0.5 op_sel_hi:[1,0]
	v_med3_f32 v170, v170, s47, v225
	v_med3_f32 v171, v171, s47, v225
	v_pk_mul_f32 v[172:173], v[170:171], v[170:171]
	s_nop 0
	v_pk_fma_f32 v[176:177], v[172:173], s[34:35], v[148:149] op_sel_hi:[1,0,0] neg_lo:[1,0,0] neg_hi:[1,0,0]
	s_nop 0
	v_pk_fma_f32 v[176:177], v[172:173], v[176:177], s[38:39] op_sel_hi:[1,1,0]
	s_nop 0
	v_pk_fma_f32 v[176:177], v[172:173], v[176:177], s[40:41] op_sel_hi:[1,1,0]
	s_nop 0
	v_pk_fma_f32 v[176:177], v[172:173], v[176:177], s[42:43] op_sel_hi:[1,1,0]
	s_nop 0
	v_pk_fma_f32 v[176:177], v[172:173], v[176:177], s[44:45] op_sel_hi:[1,1,0]
	s_nop 0
	v_pk_fma_f32 v[176:177], v[172:173], v[176:177], s[46:47] op_sel_hi:[1,1,0]
	s_nop 0
	v_pk_fma_f32 v[172:173], v[172:173], v[176:177], s[48:49] op_sel_hi:[1,1,0]
	s_waitcnt vmcnt(0)
; __device__ __forceinline__ unsigned cvt_pk_bf16(float lo, float hi) { unsigned r; asm volatile("v_cvt_pk_bf16_f32 %0, %1, %2" : "=v"(r) : "v"(lo), "v"(hi)); return r; }
;     static __device__ __forceinline__ void finish(const float (&g0)[4], const float (&g1)[4], const float (&g2)[4], const float (&w0)[4], const float (&w1)[4], const float (&w2)[4], const float (&bb)[4],
;                                                   const f32x4 v, float rs, bf16_t* dst) {
;         float h[4];
; #pragma unroll
;         for (int j = 0; j < 4; j += 2) {
;             const f32x2 gc = (f32x2){bb[j] + w0[j] * g2[j] + w1[j] * g1[j] + w2[j] * g0[j], bb[j + 1] + w0[j + 1] * g2[j + 1] + w1[j + 1] * g1[j + 1] + w2[j + 1] * g0[j + 1]};
;             const f32x2 ge = gelu_pk(gc); h[j] = ge.x * v[j] * rs; h[j + 1] = ge.y * v[j + 1] * rs; }
;         u32x2 w; w.x = cvt_pk_bf16(h[0], h[1]); w.y = cvt_pk_bf16(h[2], h[3]);
;         *(u32x2*)dst = w;
;     __device__ __forceinline__ void operator()(const f32x4 (&acc)[2][2][4][2], const Unit& u, int wr, int wc, int fr, int fq) const {
;     ...
;                 for (int m = 0; m < 4; ++m) { const int row = row0 + m * 16; gq[m] = *(const u32x2*)(G + (size_t)row * 2816 + col); }
; #pragma unroll
;                 for (int mh = 0; mh < 4; mh += 2) {
;                 f32x4 c0[4], c1[4];
; #pragma unroll
;                 for (int m = mh; m < mh + 2; ++m) { const int row = row0 + m * 16; const float* cx = ctx + (size_t)((row - 32768) >> 3) * 2 * 2816 + col;
;                     c0[m] = *(const f32x4*)cx; c1[m] = *(const f32x4*)(cx + 2816); }
; #pragma unroll
;                 for (int m = mh; m < mh + 2; ++m) { const int row = row0 + m * 16; const u32x2 cur = gq[m];
;                     const u32x2 q1 = dpp_prev<1>(cur, cur), q2 = dpp_prev<2>(cur, cur);
;                     float g0[4], g1[4], g2[4]; unpk4(cur, g0); unpk4(q1, g1); unpk4(q2, g2);
; #pragma unroll
;                     for (int j = 0; j < 4; ++j) { const float x1 = c1[m][j], x0 = c0[m][j];
;                         if (i < 1) g1[j] = x1;
;                         if (i < 2) g2[j] = (i == 1) ? x1 : x0; }
;                     finish(g0, g1, g2, w0, w1, w2, bb, acc[0][bj][m][hv], rs8[0][m], H + (size_t)row * 2816 + col); }
	v_cndmask_b32_e32 v177, v178, v212, vcc
	v_pk_mul_f32 v[170:171], v[170:171], v[172:173]
	v_cndmask_b32_e32 v178, v179, v213, vcc
	v_pk_fma_f32 v[164:165], v[164:165], v[170:171], v[164:165]
	s_nop 0
	v_mul_f32_e32 v164, v110, v164
	v_mul_f32_e32 v170, v184, v164
	v_mul_f32_e32 v164, v111, v165
	v_mul_f32_e32 v165, v184, v164
	v_cvt_pk_bf16_f32 v164, v169, v182
	v_cvt_pk_bf16_f32 v165, v170, v165
	global_store_dwordx2 v[174:175], v[164:165], off sc1
	v_mov_b32_dpp v169, v160 row_ror:2 row_mask:0xf bank_mask:0xf bound_ctrl:1
	v_mov_b32_dpp v165, v161 row_ror:1 row_mask:0xf bank_mask:0xf bound_ctrl:1
	v_mov_b32_dpp v170, v161 row_ror:2 row_mask:0xf bank_mask:0xf bound_ctrl:1
	v_mov_b32_dpp v164, v160 row_ror:1 row_mask:0xf bank_mask:0xf bound_ctrl:1
	v_mov_b32_dpp v165, v161 row_shr:1 row_mask:0xf bank_mask:0xf
	v_mov_b32_dpp v169, v160 row_shr:2 row_mask:0xf bank_mask:0xf
	v_mov_b32_dpp v170, v161 row_shr:2 row_mask:0xf bank_mask:0xf
	v_lshlrev_b32_e32 v172, 16, v165
	v_mov_b32_dpp v164, v160 row_shr:1 row_mask:0xf bank_mask:0xf
	v_lshlrev_b32_e32 v174, 16, v169
	v_and_b32_e32 v169, 0xffff0000, v169
	v_lshlrev_b32_e32 v175, 16, v170
	v_and_b32_e32 v176, 0xffff0000, v170
	v_cndmask_b32_e64 v170, v172, v214, s[0:1]
	v_cndmask_b32_e32 v172, v180, v214, vcc
	v_lshlrev_b32_e32 v171, 16, v164
	v_and_b32_e32 v164, 0xffff0000, v164
	v_and_b32_e32 v173, 0xffff0000, v165
	v_cndmask_b32_e64 v172, v175, v172, s[8:9]
	v_cndmask_b32_e64 v175, v169, v178, s[8:9]
	v_cndmask_b32_e64 v174, v174, v177, s[8:9]
	v_cndmask_b32_e64 v165, v164, v213, s[0:1]
	v_cndmask_b32_e64 v164, v171, v212, s[0:1]
	v_cndmask_b32_e64 v171, v173, v215, s[0:1]
	v_cndmask_b32_e32 v173, v181, v215, vcc
	v_pk_fma_f32 v[140:141], v[140:141], v[174:175], v[144:145]
	v_cndmask_b32_e64 v173, v176, v173, s[8:9]
	v_lshlrev_b32_e32 v176, 16, v160
	v_and_b32_e32 v177, 0xffff0000, v160
	v_pk_fma_f32 v[136:137], v[136:137], v[164:165], v[140:141]
	v_pk_fma_f32 v[142:143], v[142:143], v[172:173], v[146:147]
	v_pk_fma_f32 v[132:133], v[132:133], v[176:177], v[136:137]
	v_pk_fma_f32 v[138:139], v[138:139], v[170:171], v[142:143]
	v_pk_mul_f32 v[136:137], v[132:133], s[30:31] op_sel_hi:[1,0]
	v_pk_mul_f32 v[132:133], v[132:133], 0.5 op_sel_hi:[1,0]
	v_med3_f32 v136, v136, s47, v225
	v_med3_f32 v137, v137, s47, v225
	v_pk_mul_f32 v[140:141], v[136:137], v[136:137]
	s_nop 0
	v_pk_fma_f32 v[142:143], v[140:141], s[34:35], v[148:149] op_sel_hi:[1,0,0] neg_lo:[1,0,0] neg_hi:[1,0,0]
	s_nop 0
	v_pk_fma_f32 v[142:143], v[140:141], v[142:143], s[38:39] op_sel_hi:[1,1,0]
	s_nop 0
	v_pk_fma_f32 v[142:143], v[140:141], v[142:143], s[40:41] op_sel_hi:[1,1,0]
	s_nop 0
	v_pk_fma_f32 v[142:143], v[140:141], v[142:143], s[42:43] op_sel_hi:[1,1,0]
	s_nop 0
	v_pk_fma_f32 v[142:143], v[140:141], v[142:143], s[44:45] op_sel_hi:[1,1,0]
	s_nop 0
	v_pk_fma_f32 v[142:143], v[140:141], v[142:143], s[46:47] op_sel_hi:[1,1,0]
	s_nop 0
	v_pk_fma_f32 v[140:141], v[140:141], v[142:143], s[48:49] op_sel_hi:[1,1,0]
	s_nop 0
	v_pk_mul_f32 v[136:137], v[136:137], v[140:141]
	s_nop 0
	v_pk_fma_f32 v[132:133], v[132:133], v[136:137], v[132:133]
	s_nop 0
	v_mul_f32_e32 v132, v100, v132
	v_mul_f32_e32 v140, v2, v132
	v_mul_f32_e32 v132, v101, v133
	v_mul_f32_e32 v141, v2, v132
	v_lshlrev_b32_e32 v132, 16, v161
	v_and_b32_e32 v133, 0xffff0000, v161
	v_pk_fma_f32 v[132:133], v[134:135], v[132:133], v[138:139]
	s_nop 0
	v_pk_mul_f32 v[134:135], v[132:133], s[30:31] op_sel_hi:[1,0]
	v_pk_mul_f32 v[132:133], v[132:133], 0.5 op_sel_hi:[1,0]
	v_med3_f32 v134, v134, s47, v225
	v_med3_f32 v135, v135, s47, v225
	v_pk_mul_f32 v[136:137], v[134:135], v[134:135]
	s_nop 0
	v_pk_fma_f32 v[138:139], v[136:137], s[34:35], v[148:149] op_sel_hi:[1,0,0] neg_lo:[1,0,0] neg_hi:[1,0,0]
	s_nop 0
	v_pk_fma_f32 v[138:139], v[136:137], v[138:139], s[38:39] op_sel_hi:[1,1,0]
	s_nop 0
	v_pk_fma_f32 v[138:139], v[136:137], v[138:139], s[40:41] op_sel_hi:[1,1,0]
	s_nop 0
	v_pk_fma_f32 v[138:139], v[136:137], v[138:139], s[42:43] op_sel_hi:[1,1,0]
	s_nop 0
	v_pk_fma_f32 v[138:139], v[136:137], v[138:139], s[44:45] op_sel_hi:[1,1,0]
	s_nop 0
	v_pk_fma_f32 v[138:139], v[136:137], v[138:139], s[46:47] op_sel_hi:[1,1,0]
	s_nop 0
	v_pk_fma_f32 v[136:137], v[136:137], v[138:139], s[48:49] op_sel_hi:[1,1,0]
	s_nop 0
	v_pk_mul_f32 v[134:135], v[134:135], v[136:137]
	s_nop 0
	v_pk_fma_f32 v[132:133], v[132:133], v[134:135], v[132:133]
	s_nop 0
	v_mul_f32_e32 v132, v102, v132
	v_mul_f32_e32 v134, v2, v132
	v_mul_f32_e32 v132, v103, v133
	v_mul_f32_e32 v133, v2, v132
	v_cvt_pk_bf16_f32 v132, v140, v141
	v_cvt_pk_bf16_f32 v133, v134, v133
	global_store_dwordx2 v[162:163], v[132:133], off sc1
	v_add_u32_e32 v132, 0x80, v150
	v_ashrrev_i32_e32 v133, 31, v132
	v_lshlrev_b64 v[162:163], 1, v[132:133]
	v_lshl_add_u64 v[160:161], s[68:69], 0, v[162:163]
	v_lshlrev_b64 v[132:133], 2, v[132:133]
	v_mad_i64_i32 v[134:135], s[10:11], v210, s91, v[160:161]
	v_lshl_add_u64 v[226:227], s[82:83], 0, v[132:133]
	global_load_dwordx2 v[182:183], v[134:135], off
	v_mad_i64_i32 v[134:135], s[10:11], v151, s45, v[226:227]
	v_add_co_u32_e64 v136, s[10:11], s41, v134
	s_waitcnt vmcnt(0)
; __device__ __forceinline__ unsigned cvt_pk_bf16(float lo, float hi) { unsigned r; asm volatile("v_cvt_pk_bf16_f32 %0, %1, %2" : "=v"(r) : "v"(lo), "v"(hi)); return r; }
;     static __device__ __forceinline__ void finish(const float (&g0)[4], const float (&g1)[4], const float (&g2)[4], const float (&w0)[4], const float (&w1)[4], const float (&w2)[4], const float (&bb)[4],
;                                                   const f32x4 v, float rs, bf16_t* dst) {
;         float h[4];
; #pragma unroll
;         for (int j = 0; j < 4; j += 2) {
;             const f32x2 gc = (f32x2){bb[j] + w0[j] * g2[j] + w1[j] * g1[j] + w2[j] * g0[j], bb[j + 1] + w0[j + 1] * g2[j + 1] + w1[j + 1] * g1[j + 1] + w2[j + 1] * g0[j + 1]};
;             const f32x2 ge = gelu_pk(gc); h[j] = ge.x * v[j] * rs; h[j + 1] = ge.y * v[j + 1] * rs; }
;         u32x2 w; w.x = cvt_pk_bf16(h[0], h[1]); w.y = cvt_pk_bf16(h[2], h[3]);
;         *(u32x2*)dst = w;
;     __device__ __forceinline__ void operator()(const f32x4 (&acc)[2][2][4][2], const Unit& u, int wr, int wc, int fr, int fq) const {
;     ...
;                 for (int m = 0; m < 4; ++m) { const int row = row0 + m * 16; gq[m] = *(const u32x2*)(G + (size_t)row * 2816 + col); }
; #pragma unroll
;                 for (int mh = 0; mh < 4; mh += 2) {
;                 f32x4 c0[4], c1[4];
; #pragma unroll
;                 for (int m = mh; m < mh + 2; ++m) { const int row = row0 + m * 16; const float* cx = ctx + (size_t)((row - 32768) >> 3) * 2 * 2816 + col;
;                     c0[m] = *(const f32x4*)cx; c1[m] = *(const f32x4*)(cx + 2816); }
; #pragma unroll
;                 for (int m = mh; m < mh + 2; ++m) { const int row = row0 + m * 16; const u32x2 cur = gq[m];
;                     const u32x2 q1 = dpp_prev<1>(cur, cur), q2 = dpp_prev<2>(cur, cur);
;                     float g0[4], g1[4], g2[4]; unpk4(cur, g0); unpk4(q1, g1); unpk4(q2, g2);
; #pragma unroll
;                     for (int j = 0; j < 4; ++j) { const float x1 = c1[m][j], x0 = c0[m][j];
;                         if (i < 1) g1[j] = x1;
;                         if (i < 2) g2[j] = (i == 1) ? x1 : x0; }
;                     finish(g0, g1, g2, w0, w1, w2, bb, acc[0][bj][m][hv], rs8[0][m], H + (size_t)row * 2816 + col); }
	v_mov_b32_dpp v169, v182 row_ror:1 row_mask:0xf bank_mask:0xf bound_ctrl:1
	v_addc_co_u32_e64 v137, s[10:11], 0, v135, s[10:11]
	global_load_dwordx4 v[170:173], v[136:137], off offset:3072
	global_load_dwordx4 v[174:177], v[134:135], off
	v_lshl_add_u64 v[134:135], s[66:67], 0, v[132:133]
	global_load_dwordx4 v[140:143], v[134:135], off
	v_lshl_add_u64 v[134:135], s[88:89], 0, v[132:133]
	global_load_dwordx4 v[144:147], v[134:135], off
	v_lshl_add_u64 v[134:135], s[52:53], 0, v[132:133]
	global_load_dwordx4 v[136:139], v[134:135], off
	v_lshl_add_u64 v[132:133], s[54:55], 0, v[132:133]
	global_load_dwordx4 v[132:135], v[132:133], off
	v_mad_i64_i32 v[164:165], s[10:11], v194, s91, v[160:161]
	v_mad_i64_i32 v[178:179], s[10:11], v192, s91, v[160:161]
	v_mad_i64_i32 v[160:161], s[10:11], v190, s91, v[160:161]
	global_load_dwordx2 v[228:229], v[164:165], off
	s_nop 0
	global_load_dwordx2 v[164:165], v[178:179], off
	s_nop 0
	global_load_dwordx2 v[160:161], v[160:161], off
	v_mad_i64_i32 v[178:179], s[10:11], v168, s45, v[226:227]
	v_add_co_u32_e64 v212, s[10:11], s41, v178
	v_mov_b32_dpp v169, v182 row_shr:1 row_mask:0xf bank_mask:0xf
	s_nop 0
	v_addc_co_u32_e64 v213, s[10:11], 0, v179, s[10:11]
	global_load_dwordx4 v[178:181], v[178:179], off
	s_nop 0
	global_load_dwordx4 v[212:215], v[212:213], off offset:3072
	v_mov_b32_dpp v185, v183 row_ror:1 row_mask:0xf bank_mask:0xf bound_ctrl:1
	v_mov_b32_dpp v187, v182 row_ror:2 row_mask:0xf bank_mask:0xf bound_ctrl:1
	v_lshlrev_b32_e32 v191, 16, v169
	v_mov_b32_dpp v185, v183 row_shr:1 row_mask:0xf bank_mask:0xf
	v_mov_b32_dpp v187, v182 row_shr:2 row_mask:0xf bank_mask:0xf
	v_and_b32_e32 v169, 0xffff0000, v169
	v_lshlrev_b32_e32 v193, 16, v185
	v_and_b32_e32 v185, 0xffff0000, v185
	v_lshlrev_b32_e32 v195, 16, v187
	v_and_b32_e32 v187, 0xffff0000, v187
	v_mov_b32_dpp v189, v183 row_ror:2 row_mask:0xf bank_mask:0xf bound_ctrl:1
	s_waitcnt vmcnt(10)
	v_cndmask_b32_e64 v231, v169, v171, s[0:1]
	s_waitcnt vmcnt(9)
	v_cndmask_b32_e32 v169, v174, v170, vcc
	v_cndmask_b32_e32 v174, v175, v171, vcc
	v_cndmask_b32_e64 v230, v191, v170, s[0:1]
	v_cndmask_b32_e64 v233, v185, v173, s[0:1]
	v_cndmask_b32_e64 v232, v193, v172, s[0:1]
	v_cndmask_b32_e32 v170, v176, v172, vcc
	v_cndmask_b32_e32 v171, v177, v173, vcc
	v_cndmask_b32_e64 v173, v187, v174, s[8:9]
	v_cndmask_b32_e64 v172, v195, v169, s[8:9]
	s_waitcnt vmcnt(7)
	v_pk_fma_f32 v[172:173], v[140:141], v[172:173], v[144:145]
	v_lshlrev_b32_e32 v176, 16, v182
	v_and_b32_e32 v177, 0xffff0000, v182
	s_waitcnt vmcnt(6)
	v_pk_fma_f32 v[172:173], v[136:137], v[230:231], v[172:173]
	v_mov_b32_dpp v189, v183 row_shr:2 row_mask:0xf bank_mask:0xf
	s_waitcnt vmcnt(5)
	v_pk_fma_f32 v[172:173], v[132:133], v[176:177], v[172:173]
	v_lshlrev_b32_e32 v211, 16, v189
	v_and_b32_e32 v189, 0xffff0000, v189
	v_pk_mul_f32 v[176:177], v[172:173], s[30:31] op_sel_hi:[1,0]
	v_cndmask_b32_e64 v171, v189, v171, s[8:9]
	v_cndmask_b32_e64 v170, v211, v170, s[8:9]
	v_med3_f32 v176, v176, s47, v225
	v_med3_f32 v177, v177, s47, v225
	v_pk_fma_f32 v[170:171], v[142:143], v[170:171], v[146:147]
	v_pk_mul_f32 v[230:231], v[176:177], v[176:177]
	v_pk_fma_f32 v[170:171], v[138:139], v[232:233], v[170:171]
	v_pk_fma_f32 v[232:233], v[230:231], s[34:35], v[148:149] op_sel_hi:[1,0,0] neg_lo:[1,0,0] neg_hi:[1,0,0]
	v_pk_mul_f32 v[172:173], v[172:173], 0.5 op_sel_hi:[1,0]
	v_pk_fma_f32 v[232:233], v[230:231], v[232:233], s[38:39] op_sel_hi:[1,1,0]
	v_lshl_add_u64 v[174:175], v[152:153], 0, v[162:163]
	v_pk_fma_f32 v[232:233], v[230:231], v[232:233], s[40:41] op_sel_hi:[1,1,0]
	s_nop 0
	v_pk_fma_f32 v[232:233], v[230:231], v[232:233], s[42:43] op_sel_hi:[1,1,0]
	s_nop 0
	v_pk_fma_f32 v[232:233], v[230:231], v[232:233], s[44:45] op_sel_hi:[1,1,0]
	s_nop 0
	v_pk_fma_f32 v[232:233], v[230:231], v[232:233], s[46:47] op_sel_hi:[1,1,0]
	s_nop 0
	v_pk_fma_f32 v[230:231], v[230:231], v[232:233], s[48:49] op_sel_hi:[1,1,0]
	s_nop 0
	v_pk_mul_f32 v[176:177], v[176:177], v[230:231]
	s_nop 0
	v_pk_fma_f32 v[172:173], v[172:173], v[176:177], v[172:173]
	s_nop 0
	v_mul_f32_e32 v169, v68, v172
	v_mul_f32_e32 v172, v69, v173
	v_mul_f32_e32 v185, v188, v172
	v_lshlrev_b32_e32 v172, 16, v183
	v_and_b32_e32 v173, 0xffff0000, v183
	v_pk_fma_f32 v[170:171], v[134:135], v[172:173], v[170:171]
	v_mul_f32_e32 v169, v188, v169
	v_pk_mul_f32 v[172:173], v[170:171], s[30:31] op_sel_hi:[1,0]
	v_pk_mul_f32 v[170:171], v[170:171], 0.5 op_sel_hi:[1,0]
	v_med3_f32 v172, v172, s47, v225
	v_med3_f32 v173, v173, s47, v225
	v_pk_mul_f32 v[176:177], v[172:173], v[172:173]
	s_nop 0
	v_pk_fma_f32 v[182:183], v[176:177], s[34:35], v[148:149] op_sel_hi:[1,0,0] neg_lo:[1,0,0] neg_hi:[1,0,0]
	s_nop 0
	v_pk_fma_f32 v[182:183], v[176:177], v[182:183], s[38:39] op_sel_hi:[1,1,0]
	s_nop 0
	v_pk_fma_f32 v[182:183], v[176:177], v[182:183], s[40:41] op_sel_hi:[1,1,0]
	s_nop 0
	v_pk_fma_f32 v[182:183], v[176:177], v[182:183], s[42:43] op_sel_hi:[1,1,0]
	s_nop 0
	v_pk_fma_f32 v[182:183], v[176:177], v[182:183], s[44:45] op_sel_hi:[1,1,0]
	s_nop 0
	v_pk_fma_f32 v[182:183], v[176:177], v[182:183], s[46:47] op_sel_hi:[1,1,0]
	s_nop 0
	v_pk_fma_f32 v[176:177], v[176:177], v[182:183], s[48:49] op_sel_hi:[1,1,0]
	s_nop 0
	v_pk_mul_f32 v[172:173], v[172:173], v[176:177]
	s_nop 0
	v_pk_fma_f32 v[170:171], v[170:171], v[172:173], v[170:171]
	s_nop 0
	v_mul_f32_e32 v170, v70, v170
	v_mul_f32_e32 v172, v188, v170
	v_mul_f32_e32 v170, v71, v171
	v_mul_f32_e32 v171, v188, v170
	v_cvt_pk_bf16_f32 v170, v169, v185
	v_cvt_pk_bf16_f32 v171, v172, v171
	s_waitcnt vmcnt(4)
; __device__ __forceinline__ unsigned cvt_pk_bf16(float lo, float hi) { unsigned r; asm volatile("v_cvt_pk_bf16_f32 %0, %1, %2" : "=v"(r) : "v"(lo), "v"(hi)); return r; }
;     static __device__ __forceinline__ void finish(const float (&g0)[4], const float (&g1)[4], const float (&g2)[4], const float (&w0)[4], const float (&w1)[4], const float (&w2)[4], const float (&bb)[4],
;                                                   const f32x4 v, float rs, bf16_t* dst) {
;         float h[4];
; #pragma unroll
;         for (int j = 0; j < 4; j += 2) {
;             const f32x2 gc = (f32x2){bb[j] + w0[j] * g2[j] + w1[j] * g1[j] + w2[j] * g0[j], bb[j + 1] + w0[j + 1] * g2[j + 1] + w1[j + 1] * g1[j + 1] + w2[j + 1] * g0[j + 1]};
;             const f32x2 ge = gelu_pk(gc); h[j] = ge.x * v[j] * rs; h[j + 1] = ge.y * v[j + 1] * rs; }
;         u32x2 w; w.x = cvt_pk_bf16(h[0], h[1]); w.y = cvt_pk_bf16(h[2], h[3]);
;         *(u32x2*)dst = w;
;     __device__ __forceinline__ void operator()(const f32x4 (&acc)[2][2][4][2], const Unit& u, int wr, int wc, int fr, int fq) const {
;     ...
;                 for (int m = 0; m < 4; ++m) { const int row = row0 + m * 16; gq[m] = *(const u32x2*)(G + (size_t)row * 2816 + col); }
; #pragma unroll
;                 for (int mh = 0; mh < 4; mh += 2) {
;                 f32x4 c0[4], c1[4];
; #pragma unroll
;                 for (int m = mh; m < mh + 2; ++m) { const int row = row0 + m * 16; const float* cx = ctx + (size_t)((row - 32768) >> 3) * 2 * 2816 + col;
;                     c0[m] = *(const f32x4*)cx; c1[m] = *(const f32x4*)(cx + 2816); }
; #pragma unroll
;                 for (int m = mh; m < mh + 2; ++m) { const int row = row0 + m * 16; const u32x2 cur = gq[m];
;                     const u32x2 q1 = dpp_prev<1>(cur, cur), q2 = dpp_prev<2>(cur, cur);
;                     float g0[4], g1[4], g2[4]; unpk4(cur, g0); unpk4(q1, g1); unpk4(q2, g2);
; #pragma unroll
;                     for (int j = 0; j < 4; ++j) { const float x1 = c1[m][j], x0 = c0[m][j];
;                         if (i < 1) g1[j] = x1;
;                         if (i < 2) g2[j] = (i == 1) ? x1 : x0; }
;                     finish(g0, g1, g2, w0, w1, w2, bb, acc[0][bj][m][hv], rs8[0][m], H + (size_t)row * 2816 + col); }
	v_mov_b32_dpp v169, v228 row_ror:1 row_mask:0xf bank_mask:0xf bound_ctrl:1
	global_store_dwordx2 v[174:175], v[170:171], off sc1
	v_mov_b32_dpp v171, v228 row_ror:2 row_mask:0xf bank_mask:0xf bound_ctrl:1
	v_mov_b32_dpp v169, v228 row_shr:1 row_mask:0xf bank_mask:0xf
	v_mov_b32_dpp v170, v229 row_ror:1 row_mask:0xf bank_mask:0xf bound_ctrl:1
	v_mov_b32_dpp v171, v228 row_shr:2 row_mask:0xf bank_mask:0xf
	v_lshlrev_b32_e32 v173, 16, v169
	v_and_b32_e32 v169, 0xffff0000, v169
	v_mov_b32_dpp v170, v229 row_shr:1 row_mask:0xf bank_mask:0xf
	v_mov_b32_dpp v172, v229 row_ror:2 row_mask:0xf bank_mask:0xf bound_ctrl:1
	v_lshlrev_b32_e32 v176, 16, v171
	v_and_b32_e32 v177, 0xffff0000, v171
	s_waitcnt vmcnt(1)
	v_cndmask_b32_e64 v171, v169, v213, s[0:1]
	v_cndmask_b32_e32 v169, v178, v212, vcc
	v_cndmask_b32_e32 v178, v179, v213, vcc
	v_mov_b32_dpp v172, v229 row_shr:2 row_mask:0xf bank_mask:0xf
	v_lshlrev_b32_e32 v174, 16, v170
	v_and_b32_e32 v175, 0xffff0000, v170
	v_cndmask_b32_e64 v177, v177, v178, s[8:9]
	v_cndmask_b32_e64 v176, v176, v169, s[8:9]
	v_lshlrev_b32_e32 v182, 16, v172
	v_and_b32_e32 v183, 0xffff0000, v172
	v_cndmask_b32_e64 v170, v173, v212, s[0:1]
	v_cndmask_b32_e64 v173, v175, v215, s[0:1]
	v_cndmask_b32_e64 v172, v174, v214, s[0:1]
	v_cndmask_b32_e32 v174, v180, v214, vcc
	v_cndmask_b32_e32 v175, v181, v215, vcc
	v_pk_fma_f32 v[176:177], v[140:141], v[176:177], v[144:145]
	v_cndmask_b32_e64 v175, v183, v175, s[8:9]
	v_cndmask_b32_e64 v174, v182, v174, s[8:9]
	v_lshlrev_b32_e32 v180, 16, v228
	v_and_b32_e32 v181, 0xffff0000, v228
	v_pk_fma_f32 v[170:171], v[136:137], v[170:171], v[176:177]
	v_pk_fma_f32 v[174:175], v[142:143], v[174:175], v[146:147]
	v_pk_fma_f32 v[170:171], v[132:133], v[180:181], v[170:171]
	v_pk_fma_f32 v[172:173], v[138:139], v[172:173], v[174:175]
	v_pk_mul_f32 v[174:175], v[170:171], s[30:31] op_sel_hi:[1,0]
	v_pk_mul_f32 v[170:171], v[170:171], 0.5 op_sel_hi:[1,0]
	v_med3_f32 v174, v174, s47, v225
	v_med3_f32 v175, v175, s47, v225
	v_pk_mul_f32 v[176:177], v[174:175], v[174:175]
	v_lshl_add_u64 v[178:179], v[154:155], 0, v[162:163]
	v_pk_fma_f32 v[180:181], v[176:177], s[34:35], v[148:149] op_sel_hi:[1,0,0] neg_lo:[1,0,0] neg_hi:[1,0,0]
	v_mov_b32_dpp v185, v165 row_ror:2 row_mask:0xf bank_mask:0xf bound_ctrl:1
	v_pk_fma_f32 v[180:181], v[176:177], v[180:181], s[38:39] op_sel_hi:[1,1,0]
	s_nop 0
	v_pk_fma_f32 v[180:181], v[176:177], v[180:181], s[40:41] op_sel_hi:[1,1,0]
	v_mov_b32_dpp v185, v165 row_shr:2 row_mask:0xf bank_mask:0xf
	v_pk_fma_f32 v[180:181], v[176:177], v[180:181], s[42:43] op_sel_hi:[1,1,0]
	v_lshlrev_b32_e32 v211, 16, v185
	v_pk_fma_f32 v[180:181], v[176:177], v[180:181], s[44:45] op_sel_hi:[1,1,0]
	v_and_b32_e32 v185, 0xffff0000, v185
	v_pk_fma_f32 v[180:181], v[176:177], v[180:181], s[46:47] op_sel_hi:[1,1,0]
	s_nop 0
	v_pk_fma_f32 v[176:177], v[176:177], v[180:181], s[48:49] op_sel_hi:[1,1,0]
	s_nop 0
	v_pk_mul_f32 v[174:175], v[174:175], v[176:177]
	s_nop 0
	v_pk_fma_f32 v[170:171], v[170:171], v[174:175], v[170:171]
	s_nop 0
	v_mul_f32_e32 v169, v56, v170
	v_mul_f32_e32 v170, v57, v171
	v_mul_f32_e32 v180, v186, v170
	v_lshlrev_b32_e32 v170, 16, v229
	v_and_b32_e32 v171, 0xffff0000, v229
	v_pk_fma_f32 v[170:171], v[134:135], v[170:171], v[172:173]
	v_mul_f32_e32 v169, v186, v169
	v_pk_mul_f32 v[172:173], v[170:171], s[30:31] op_sel_hi:[1,0]
	v_pk_mul_f32 v[170:171], v[170:171], 0.5 op_sel_hi:[1,0]
	v_med3_f32 v172, v172, s47, v225
	v_med3_f32 v173, v173, s47, v225
	v_pk_mul_f32 v[174:175], v[172:173], v[172:173]
	s_nop 0
	v_pk_fma_f32 v[176:177], v[174:175], s[34:35], v[148:149] op_sel_hi:[1,0,0] neg_lo:[1,0,0] neg_hi:[1,0,0]
	s_nop 0
	v_pk_fma_f32 v[176:177], v[174:175], v[176:177], s[38:39] op_sel_hi:[1,1,0]
	s_nop 0
	v_pk_fma_f32 v[176:177], v[174:175], v[176:177], s[40:41] op_sel_hi:[1,1,0]
	s_nop 0
	v_pk_fma_f32 v[176:177], v[174:175], v[176:177], s[42:43] op_sel_hi:[1,1,0]
	s_nop 0
	v_pk_fma_f32 v[176:177], v[174:175], v[176:177], s[44:45] op_sel_hi:[1,1,0]
	s_nop 0
	v_pk_fma_f32 v[176:177], v[174:175], v[176:177], s[46:47] op_sel_hi:[1,1,0]
	s_nop 0
	v_pk_fma_f32 v[174:175], v[174:175], v[176:177], s[48:49] op_sel_hi:[1,1,0]
	s_nop 0
	v_pk_mul_f32 v[172:173], v[172:173], v[174:175]
	v_mad_i64_i32 v[174:175], s[10:11], v166, s45, v[226:227]
	v_pk_fma_f32 v[170:171], v[170:171], v[172:173], v[170:171]
	s_nop 0
	v_mul_f32_e32 v170, v58, v170
	v_mul_f32_e32 v172, v186, v170
	v_mul_f32_e32 v170, v59, v171
	v_mul_f32_e32 v171, v186, v170
	v_cvt_pk_bf16_f32 v170, v169, v180
	v_cvt_pk_bf16_f32 v171, v172, v171
	global_store_dwordx2 v[178:179], v[170:171], off sc1
	v_add_co_u32_e64 v170, s[10:11], s41, v174
	v_mov_b32_dpp v169, v164 row_ror:1 row_mask:0xf bank_mask:0xf bound_ctrl:1
	s_nop 0
	v_addc_co_u32_e64 v171, s[10:11], 0, v175, s[10:11]
	global_load_dwordx4 v[170:173], v[170:171], off offset:3072
	s_nop 0
	global_load_dwordx4 v[174:177], v[174:175], off
	v_mad_i64_i32 v[178:179], s[10:11], v167, s45, v[226:227]
	v_add_co_u32_e64 v182, s[10:11], s41, v178
	v_mov_b32_dpp v169, v164 row_shr:1 row_mask:0xf bank_mask:0xf
	s_nop 0
	v_addc_co_u32_e64 v183, s[10:11], 0, v179, s[10:11]
	global_load_dwordx4 v[178:181], v[178:179], off
	s_nop 0
	global_load_dwordx4 v[212:215], v[182:183], off offset:3072
	v_mov_b32_dpp v182, v165 row_ror:1 row_mask:0xf bank_mask:0xf bound_ctrl:1
	v_mov_b32_dpp v183, v164 row_ror:2 row_mask:0xf bank_mask:0xf bound_ctrl:1
	v_lshlrev_b32_e32 v187, 16, v169
	v_mov_b32_dpp v182, v165 row_shr:1 row_mask:0xf bank_mask:0xf
	v_mov_b32_dpp v183, v164 row_shr:2 row_mask:0xf bank_mask:0xf
	v_and_b32_e32 v169, 0xffff0000, v169
	v_lshlrev_b32_e32 v189, 16, v182
	v_and_b32_e32 v191, 0xffff0000, v182
	v_lshlrev_b32_e32 v193, 16, v183
	v_and_b32_e32 v195, 0xffff0000, v183
	s_waitcnt vmcnt(3)
; __device__ __forceinline__ unsigned cvt_pk_bf16(float lo, float hi) { unsigned r; asm volatile("v_cvt_pk_bf16_f32 %0, %1, %2" : "=v"(r) : "v"(lo), "v"(hi)); return r; }
;     static __device__ __forceinline__ void finish(const float (&g0)[4], const float (&g1)[4], const float (&g2)[4], const float (&w0)[4], const float (&w1)[4], const float (&w2)[4], const float (&bb)[4],
;                                                   const f32x4 v, float rs, bf16_t* dst) {
;         float h[4];
; #pragma unroll
;         for (int j = 0; j < 4; j += 2) {
;             const f32x2 gc = (f32x2){bb[j] + w0[j] * g2[j] + w1[j] * g1[j] + w2[j] * g0[j], bb[j + 1] + w0[j + 1] * g2[j + 1] + w1[j + 1] * g1[j + 1] + w2[j + 1] * g0[j + 1]};
;             const f32x2 ge = gelu_pk(gc); h[j] = ge.x * v[j] * rs; h[j + 1] = ge.y * v[j + 1] * rs; }
;         u32x2 w; w.x = cvt_pk_bf16(h[0], h[1]); w.y = cvt_pk_bf16(h[2], h[3]);
;         *(u32x2*)dst = w;
;     __device__ __forceinline__ void operator()(const f32x4 (&acc)[2][2][4][2], const Unit& u, int wr, int wc, int fr, int fq) const {
;     ...
;                 for (int m = 0; m < 4; ++m) { const int row = row0 + m * 16; gq[m] = *(const u32x2*)(G + (size_t)row * 2816 + col); }
; #pragma unroll
;                 for (int mh = 0; mh < 4; mh += 2) {
;                 f32x4 c0[4], c1[4];
; #pragma unroll
;                 for (int m = mh; m < mh + 2; ++m) { const int row = row0 + m * 16; const float* cx = ctx + (size_t)((row - 32768) >> 3) * 2 * 2816 + col;
;                     c0[m] = *(const f32x4*)cx; c1[m] = *(const f32x4*)(cx + 2816); }
; #pragma unroll
;                 for (int m = mh; m < mh + 2; ++m) { const int row = row0 + m * 16; const u32x2 cur = gq[m];
;                     const u32x2 q1 = dpp_prev<1>(cur, cur), q2 = dpp_prev<2>(cur, cur);
;                     float g0[4], g1[4], g2[4]; unpk4(cur, g0); unpk4(q1, g1); unpk4(q2, g2);
; #pragma unroll
;                     for (int j = 0; j < 4; ++j) { const float x1 = c1[m][j], x0 = c0[m][j];
;                         if (i < 1) g1[j] = x1;
;                         if (i < 2) g2[j] = (i == 1) ? x1 : x0; }
;                     finish(g0, g1, g2, w0, w1, w2, bb, acc[0][bj][m][hv], rs8[0][m], H + (size_t)row * 2816 + col); }
	v_cndmask_b32_e64 v183, v169, v171, s[0:1]
	s_waitcnt vmcnt(2)
	v_cndmask_b32_e32 v169, v174, v170, vcc
	v_cndmask_b32_e32 v174, v175, v171, vcc
	v_cndmask_b32_e64 v182, v187, v170, s[0:1]
	v_cndmask_b32_e64 v227, v191, v173, s[0:1]
	v_cndmask_b32_e64 v226, v189, v172, s[0:1]
	v_cndmask_b32_e32 v170, v176, v172, vcc
	v_cndmask_b32_e32 v171, v177, v173, vcc
	v_cndmask_b32_e64 v173, v195, v174, s[8:9]
	v_cndmask_b32_e64 v172, v193, v169, s[8:9]
	v_pk_fma_f32 v[172:173], v[140:141], v[172:173], v[144:145]
	v_lshlrev_b32_e32 v176, 16, v164
	v_and_b32_e32 v177, 0xffff0000, v164
	v_pk_fma_f32 v[172:173], v[136:137], v[182:183], v[172:173]
	v_cndmask_b32_e64 v171, v185, v171, s[8:9]
	v_pk_fma_f32 v[172:173], v[132:133], v[176:177], v[172:173]
	v_cndmask_b32_e64 v170, v211, v170, s[8:9]
	v_pk_mul_f32 v[176:177], v[172:173], s[30:31] op_sel_hi:[1,0]
	v_pk_fma_f32 v[170:171], v[142:143], v[170:171], v[146:147]
	v_med3_f32 v176, v176, s47, v225
	v_med3_f32 v177, v177, s47, v225
	v_pk_mul_f32 v[182:183], v[176:177], v[176:177]
	v_pk_fma_f32 v[170:171], v[138:139], v[226:227], v[170:171]
	v_pk_fma_f32 v[226:227], v[182:183], s[34:35], v[148:149] op_sel_hi:[1,0,0] neg_lo:[1,0,0] neg_hi:[1,0,0]
	v_pk_mul_f32 v[172:173], v[172:173], 0.5 op_sel_hi:[1,0]
	v_pk_fma_f32 v[226:227], v[182:183], v[226:227], s[38:39] op_sel_hi:[1,1,0]
	v_lshl_add_u64 v[174:175], v[156:157], 0, v[162:163]
	v_pk_fma_f32 v[226:227], v[182:183], v[226:227], s[40:41] op_sel_hi:[1,1,0]
	v_lshl_add_u64 v[162:163], v[158:159], 0, v[162:163]
	v_pk_fma_f32 v[226:227], v[182:183], v[226:227], s[42:43] op_sel_hi:[1,1,0]
	s_nop 0
	v_pk_fma_f32 v[226:227], v[182:183], v[226:227], s[44:45] op_sel_hi:[1,1,0]
	s_nop 0
	v_pk_fma_f32 v[226:227], v[182:183], v[226:227], s[46:47] op_sel_hi:[1,1,0]
	s_nop 0
	v_pk_fma_f32 v[182:183], v[182:183], v[226:227], s[48:49] op_sel_hi:[1,1,0]
	s_nop 0
	v_pk_mul_f32 v[176:177], v[176:177], v[182:183]
	s_nop 0
	v_pk_fma_f32 v[172:173], v[172:173], v[176:177], v[172:173]
	s_nop 0
	v_mul_f32_e32 v164, v48, v172
	v_mul_f32_e32 v169, v184, v164
	v_mul_f32_e32 v164, v49, v173
	v_mul_f32_e32 v182, v184, v164
	v_lshlrev_b32_e32 v164, 16, v165
	v_and_b32_e32 v165, 0xffff0000, v165
	v_pk_fma_f32 v[164:165], v[134:135], v[164:165], v[170:171]
	s_nop 0
	v_pk_mul_f32 v[170:171], v[164:165], s[30:31] op_sel_hi:[1,0]
	v_pk_mul_f32 v[164:165], v[164:165], 0.5 op_sel_hi:[1,0]
	v_med3_f32 v170, v170, s47, v225
	v_med3_f32 v171, v171, s47, v225
	v_pk_mul_f32 v[172:173], v[170:171], v[170:171]
	s_nop 0
	v_pk_fma_f32 v[176:177], v[172:173], s[34:35], v[148:149] op_sel_hi:[1,0,0] neg_lo:[1,0,0] neg_hi:[1,0,0]
	s_nop 0
	v_pk_fma_f32 v[176:177], v[172:173], v[176:177], s[38:39] op_sel_hi:[1,1,0]
	s_nop 0
	v_pk_fma_f32 v[176:177], v[172:173], v[176:177], s[40:41] op_sel_hi:[1,1,0]
	s_nop 0
	v_pk_fma_f32 v[176:177], v[172:173], v[176:177], s[42:43] op_sel_hi:[1,1,0]
	s_nop 0
	v_pk_fma_f32 v[176:177], v[172:173], v[176:177], s[44:45] op_sel_hi:[1,1,0]
	s_nop 0
	v_pk_fma_f32 v[176:177], v[172:173], v[176:177], s[46:47] op_sel_hi:[1,1,0]
	s_nop 0
	v_pk_fma_f32 v[172:173], v[172:173], v[176:177], s[48:49] op_sel_hi:[1,1,0]
	s_waitcnt vmcnt(0)
	v_cndmask_b32_e32 v177, v178, v212, vcc
	v_pk_mul_f32 v[170:171], v[170:171], v[172:173]
	v_cndmask_b32_e32 v178, v179, v213, vcc
	v_pk_fma_f32 v[164:165], v[164:165], v[170:171], v[164:165]
	s_nop 0
	v_mul_f32_e32 v164, v50, v164
	v_mul_f32_e32 v170, v184, v164
	v_mul_f32_e32 v164, v51, v165
	v_mul_f32_e32 v165, v184, v164
	v_cvt_pk_bf16_f32 v164, v169, v182
	v_cvt_pk_bf16_f32 v165, v170, v165
	global_store_dwordx2 v[174:175], v[164:165], off sc1
	v_mov_b32_dpp v169, v160 row_ror:2 row_mask:0xf bank_mask:0xf bound_ctrl:1
	v_mov_b32_dpp v165, v161 row_ror:1 row_mask:0xf bank_mask:0xf bound_ctrl:1
	v_mov_b32_dpp v170, v161 row_ror:2 row_mask:0xf bank_mask:0xf bound_ctrl:1
	v_mov_b32_dpp v164, v160 row_ror:1 row_mask:0xf bank_mask:0xf bound_ctrl:1
	v_mov_b32_dpp v165, v161 row_shr:1 row_mask:0xf bank_mask:0xf
	v_mov_b32_dpp v169, v160 row_shr:2 row_mask:0xf bank_mask:0xf
	v_mov_b32_dpp v170, v161 row_shr:2 row_mask:0xf bank_mask:0xf
	v_lshlrev_b32_e32 v172, 16, v165
	v_mov_b32_dpp v164, v160 row_shr:1 row_mask:0xf bank_mask:0xf
	v_lshlrev_b32_e32 v174, 16, v169
	v_and_b32_e32 v169, 0xffff0000, v169
	v_lshlrev_b32_e32 v175, 16, v170
	v_and_b32_e32 v176, 0xffff0000, v170
	v_cndmask_b32_e64 v170, v172, v214, s[0:1]
	v_cndmask_b32_e32 v172, v180, v214, vcc
	v_lshlrev_b32_e32 v171, 16, v164
	v_and_b32_e32 v164, 0xffff0000, v164
	v_and_b32_e32 v173, 0xffff0000, v165
	v_cndmask_b32_e64 v172, v175, v172, s[8:9]
	v_cndmask_b32_e64 v175, v169, v178, s[8:9]
	v_cndmask_b32_e64 v174, v174, v177, s[8:9]
	v_cndmask_b32_e64 v165, v164, v213, s[0:1]
	v_cndmask_b32_e64 v164, v171, v212, s[0:1]
	v_cndmask_b32_e64 v171, v173, v215, s[0:1]
	v_cndmask_b32_e32 v173, v181, v215, vcc
	v_pk_fma_f32 v[140:141], v[140:141], v[174:175], v[144:145]
	v_cndmask_b32_e64 v173, v176, v173, s[8:9]
	v_lshlrev_b32_e32 v176, 16, v160
	v_and_b32_e32 v177, 0xffff0000, v160
	v_pk_fma_f32 v[136:137], v[136:137], v[164:165], v[140:141]
	v_pk_fma_f32 v[142:143], v[142:143], v[172:173], v[146:147]
	v_pk_fma_f32 v[132:133], v[132:133], v[176:177], v[136:137]
	v_pk_fma_f32 v[138:139], v[138:139], v[170:171], v[142:143]
	v_pk_mul_f32 v[136:137], v[132:133], s[30:31] op_sel_hi:[1,0]
	v_pk_mul_f32 v[132:133], v[132:133], 0.5 op_sel_hi:[1,0]
	v_med3_f32 v136, v136, s47, v225
	v_med3_f32 v137, v137, s47, v225
	v_pk_mul_f32 v[140:141], v[136:137], v[136:137]
	s_nop 0
	v_pk_fma_f32 v[142:143], v[140:141], s[34:35], v[148:149] op_sel_hi:[1,0,0] neg_lo:[1,0,0] neg_hi:[1,0,0]
	s_nop 0
; __device__ __forceinline__ unsigned cvt_pk_bf16(float lo, float hi) { unsigned r; asm volatile("v_cvt_pk_bf16_f32 %0, %1, %2" : "=v"(r) : "v"(lo), "v"(hi)); return r; }
;     static __device__ __forceinline__ void finish(const float (&g0)[4], const float (&g1)[4], const float (&g2)[4], const float (&w0)[4], const float (&w1)[4], const float (&w2)[4], const float (&bb)[4],
;                                                   const f32x4 v, float rs, bf16_t* dst) {
;         float h[4];
; #pragma unroll
;         for (int j = 0; j < 4; j += 2) {
;             const f32x2 gc = (f32x2){bb[j] + w0[j] * g2[j] + w1[j] * g1[j] + w2[j] * g0[j], bb[j + 1] + w0[j + 1] * g2[j + 1] + w1[j + 1] * g1[j + 1] + w2[j + 1] * g0[j + 1]};
;             const f32x2 ge = gelu_pk(gc); h[j] = ge.x * v[j] * rs; h[j + 1] = ge.y * v[j + 1] * rs; }
;         u32x2 w; w.x = cvt_pk_bf16(h[0], h[1]); w.y = cvt_pk_bf16(h[2], h[3]);
;         *(u32x2*)dst = w;
;     __device__ __forceinline__ void operator()(const f32x4 (&acc)[2][2][4][2], const Unit& u, int wr, int wc, int fr, int fq) const {
;     ...
;                 for (int m = 0; m < 4; ++m) { const int row = row0 + m * 16; gq[m] = *(const u32x2*)(G + (size_t)row * 2816 + col); }
; #pragma unroll
;                 for (int mh = 0; mh < 4; mh += 2) {
;                 f32x4 c0[4], c1[4];
; #pragma unroll
;                 for (int m = mh; m < mh + 2; ++m) { const int row = row0 + m * 16; const float* cx = ctx + (size_t)((row - 32768) >> 3) * 2 * 2816 + col;
;                     c0[m] = *(const f32x4*)cx; c1[m] = *(const f32x4*)(cx + 2816); }
; #pragma unroll
;                 for (int m = mh; m < mh + 2; ++m) { const int row = row0 + m * 16; const u32x2 cur = gq[m];
;                     const u32x2 q1 = dpp_prev<1>(cur, cur), q2 = dpp_prev<2>(cur, cur);
;                     float g0[4], g1[4], g2[4]; unpk4(cur, g0); unpk4(q1, g1); unpk4(q2, g2);
; #pragma unroll
;                     for (int j = 0; j < 4; ++j) { const float x1 = c1[m][j], x0 = c0[m][j];
;                         if (i < 1) g1[j] = x1;
;                         if (i < 2) g2[j] = (i == 1) ? x1 : x0; }
;                     finish(g0, g1, g2, w0, w1, w2, bb, acc[0][bj][m][hv], rs8[0][m], H + (size_t)row * 2816 + col); }
	v_pk_fma_f32 v[142:143], v[140:141], v[142:143], s[38:39] op_sel_hi:[1,1,0]
	s_nop 0
	v_pk_fma_f32 v[142:143], v[140:141], v[142:143], s[40:41] op_sel_hi:[1,1,0]
	s_nop 0
	v_pk_fma_f32 v[142:143], v[140:141], v[142:143], s[42:43] op_sel_hi:[1,1,0]
	s_nop 0
	v_pk_fma_f32 v[142:143], v[140:141], v[142:143], s[44:45] op_sel_hi:[1,1,0]
	s_nop 0
	v_pk_fma_f32 v[142:143], v[140:141], v[142:143], s[46:47] op_sel_hi:[1,1,0]
	s_nop 0
	v_pk_fma_f32 v[140:141], v[140:141], v[142:143], s[48:49] op_sel_hi:[1,1,0]
	s_nop 0
	v_pk_mul_f32 v[136:137], v[136:137], v[140:141]
	s_nop 0
	v_pk_fma_f32 v[132:133], v[132:133], v[136:137], v[132:133]
	s_nop 0
	v_mul_f32_e32 v132, v40, v132
	v_mul_f32_e32 v140, v2, v132
	v_mul_f32_e32 v132, v41, v133
	v_mul_f32_e32 v141, v2, v132
	v_lshlrev_b32_e32 v132, 16, v161
	v_and_b32_e32 v133, 0xffff0000, v161
	v_pk_fma_f32 v[132:133], v[134:135], v[132:133], v[138:139]
	s_nop 0
	v_pk_mul_f32 v[134:135], v[132:133], s[30:31] op_sel_hi:[1,0]
	v_pk_mul_f32 v[132:133], v[132:133], 0.5 op_sel_hi:[1,0]
	v_med3_f32 v134, v134, s47, v225
	v_med3_f32 v135, v135, s47, v225
	v_pk_mul_f32 v[136:137], v[134:135], v[134:135]
	s_nop 0
	v_pk_fma_f32 v[138:139], v[136:137], s[34:35], v[148:149] op_sel_hi:[1,0,0] neg_lo:[1,0,0] neg_hi:[1,0,0]
	s_nop 0
	v_pk_fma_f32 v[138:139], v[136:137], v[138:139], s[38:39] op_sel_hi:[1,1,0]
	s_nop 0
	v_pk_fma_f32 v[138:139], v[136:137], v[138:139], s[40:41] op_sel_hi:[1,1,0]
	s_nop 0
	v_pk_fma_f32 v[138:139], v[136:137], v[138:139], s[42:43] op_sel_hi:[1,1,0]
	s_nop 0
	v_pk_fma_f32 v[138:139], v[136:137], v[138:139], s[44:45] op_sel_hi:[1,1,0]
	s_nop 0
	v_pk_fma_f32 v[138:139], v[136:137], v[138:139], s[46:47] op_sel_hi:[1,1,0]
	s_nop 0
	v_pk_fma_f32 v[136:137], v[136:137], v[138:139], s[48:49] op_sel_hi:[1,1,0]
	s_nop 0
	v_pk_mul_f32 v[134:135], v[134:135], v[136:137]
	s_nop 0
	v_pk_fma_f32 v[132:133], v[132:133], v[134:135], v[132:133]
	s_nop 0
	v_mul_f32_e32 v132, v42, v132
	v_mul_f32_e32 v134, v2, v132
	v_mul_f32_e32 v132, v43, v133
	v_mul_f32_e32 v133, v2, v132
	v_cvt_pk_bf16_f32 v132, v140, v141
	v_cvt_pk_bf16_f32 v133, v134, v133
	global_store_dwordx2 v[162:163], v[132:133], off sc1
	v_add_u32_e32 v132, 0x84, v150
	v_ashrrev_i32_e32 v133, 31, v132
	v_lshlrev_b64 v[160:161], 1, v[132:133]
	v_lshl_add_u64 v[162:163], s[68:69], 0, v[160:161]
	v_lshlrev_b64 v[132:133], 2, v[132:133]
	v_mad_i64_i32 v[134:135], s[10:11], v210, s91, v[162:163]
	v_lshl_add_u64 v[182:183], s[82:83], 0, v[132:133]
	global_load_dwordx2 v[164:165], v[134:135], off
	v_mad_i64_i32 v[134:135], s[10:11], v151, s45, v[182:183]
	v_add_co_u32_e64 v136, s[10:11], s41, v134
	v_lshl_add_u64 v[152:153], v[152:153], 0, v[160:161]
	s_nop 0
	v_addc_co_u32_e64 v137, s[10:11], 0, v135, s[10:11]
	global_load_dwordx4 v[170:173], v[136:137], off offset:3072
	global_load_dwordx4 v[174:177], v[134:135], off
	v_lshl_add_u64 v[134:135], s[66:67], 0, v[132:133]
	global_load_dwordx4 v[140:143], v[134:135], off
	v_lshl_add_u64 v[134:135], s[88:89], 0, v[132:133]
	global_load_dwordx4 v[144:147], v[134:135], off
	v_lshl_add_u64 v[134:135], s[52:53], 0, v[132:133]
	global_load_dwordx4 v[136:139], v[134:135], off
	v_lshl_add_u64 v[132:133], s[54:55], 0, v[132:133]
	global_load_dwordx4 v[132:135], v[132:133], off
	v_mad_i64_i32 v[150:151], s[10:11], v194, s91, v[162:163]
	v_mad_i64_i32 v[178:179], s[10:11], v192, s91, v[162:163]
	v_mad_i64_i32 v[180:181], s[10:11], v190, s91, v[162:163]
	v_mad_i64_i32 v[168:169], s[10:11], v168, s45, v[182:183]
	v_add_co_u32_e64 v212, s[10:11], s41, v168
	global_load_dwordx2 v[226:227], v[150:151], off
	global_load_dwordx2 v[162:163], v[178:179], off
	s_nop 0
	global_load_dwordx2 v[150:151], v[180:181], off
	v_addc_co_u32_e64 v213, s[10:11], 0, v169, s[10:11]
	global_load_dwordx4 v[178:181], v[168:169], off
	s_nop 0
	global_load_dwordx4 v[212:215], v[212:213], off offset:3072
	v_lshl_add_u64 v[154:155], v[154:155], 0, v[160:161]
	v_lshl_add_u64 v[156:157], v[156:157], 0, v[160:161]
	v_lshl_add_u64 v[158:159], v[158:159], 0, v[160:161]
	s_mov_b64 s[54:55], s[86:87]
	s_waitcnt vmcnt(11)
	v_mov_b32_dpp v168, v164 row_ror:1 row_mask:0xf bank_mask:0xf bound_ctrl:1
	v_mov_b32_dpp v169, v165 row_ror:1 row_mask:0xf bank_mask:0xf bound_ctrl:1
	v_mov_b32_dpp v185, v164 row_ror:2 row_mask:0xf bank_mask:0xf bound_ctrl:1
	v_mov_b32_dpp v168, v164 row_shr:1 row_mask:0xf bank_mask:0xf
	v_mov_b32_dpp v169, v165 row_shr:1 row_mask:0xf bank_mask:0xf
	v_mov_b32_dpp v185, v164 row_shr:2 row_mask:0xf bank_mask:0xf
	v_lshlrev_b32_e32 v189, 16, v168
	v_and_b32_e32 v168, 0xffff0000, v168
	v_lshlrev_b32_e32 v191, 16, v169
	v_and_b32_e32 v193, 0xffff0000, v169
	v_lshlrev_b32_e32 v195, 16, v185
	v_and_b32_e32 v185, 0xffff0000, v185
	s_waitcnt vmcnt(9)
	v_cndmask_b32_e32 v174, v174, v170, vcc
	v_cndmask_b32_e32 v175, v175, v171, vcc
	v_cndmask_b32_e64 v169, v168, v171, s[0:1]
	v_cndmask_b32_e64 v168, v189, v170, s[0:1]
	v_cndmask_b32_e64 v229, v193, v173, s[0:1]
	v_cndmask_b32_e64 v228, v191, v172, s[0:1]
	v_cndmask_b32_e32 v170, v176, v172, vcc
	v_cndmask_b32_e32 v171, v177, v173, vcc
	v_cndmask_b32_e64 v173, v185, v175, s[8:9]
	v_cndmask_b32_e64 v172, v195, v174, s[8:9]
	s_waitcnt vmcnt(7)
	v_pk_fma_f32 v[172:173], v[140:141], v[172:173], v[144:145]
	v_lshlrev_b32_e32 v174, 16, v164
	v_and_b32_e32 v175, 0xffff0000, v164
	s_waitcnt vmcnt(6)
	v_pk_fma_f32 v[168:169], v[136:137], v[168:169], v[172:173]
	v_mov_b32_dpp v187, v165 row_ror:2 row_mask:0xf bank_mask:0xf bound_ctrl:1
	s_waitcnt vmcnt(5)
	v_pk_fma_f32 v[168:169], v[132:133], v[174:175], v[168:169]
	s_waitcnt vmcnt(2)
; __device__ __forceinline__ unsigned cvt_pk_bf16(float lo, float hi) { unsigned r; asm volatile("v_cvt_pk_bf16_f32 %0, %1, %2" : "=v"(r) : "v"(lo), "v"(hi)); return r; }
;     static __device__ __forceinline__ void unpk4(const u32x2 w, float (&o)[4]) { o[0] = bf_lo(w.x); o[1] = bf_hi(w.x); o[2] = bf_lo(w.y); o[3] = bf_hi(w.y); }
;     template <int N> static __device__ __forceinline__ u32x2 dpp_prev(const u32x2 pv, const u32x2 cur) { u32x2 r; r.x = dpp_prev1<N>(pv.x, cur.x); r.y = dpp_prev1<N>(pv.y, cur.y); return r; }
;     static __device__ __forceinline__ void finish(const float (&g0)[4], const float (&g1)[4], const float (&g2)[4], const float (&w0)[4], const float (&w1)[4], const float (&w2)[4], const float (&bb)[4],
;                                                   const f32x4 v, float rs, bf16_t* dst) {
;         float h[4];
; #pragma unroll
;         for (int j = 0; j < 4; j += 2) {
;             const f32x2 gc = (f32x2){bb[j] + w0[j] * g2[j] + w1[j] * g1[j] + w2[j] * g0[j], bb[j + 1] + w0[j + 1] * g2[j + 1] + w1[j + 1] * g1[j + 1] + w2[j + 1] * g0[j + 1]};
;             const f32x2 ge = gelu_pk(gc); h[j] = ge.x * v[j] * rs; h[j + 1] = ge.y * v[j + 1] * rs; }
;         u32x2 w; w.x = cvt_pk_bf16(h[0], h[1]); w.y = cvt_pk_bf16(h[2], h[3]);
;         *(u32x2*)dst = w;
;     }
;     __device__ __forceinline__ void operator()(const f32x4 (&acc)[2][2][4][2], const Unit& u, int wr, int wc, int fr, int fq) const {
;     ...
;                 for (int m = mh; m < mh + 2; ++m) { const int row = row0 + m * 16; const float* cx = ctx + (size_t)((row - 32768) >> 3) * 2 * 2816 + col;
;                     c0[m] = *(const f32x4*)cx; c1[m] = *(const f32x4*)(cx + 2816); }
; #pragma unroll
;                 for (int m = mh; m < mh + 2; ++m) { const int row = row0 + m * 16; const u32x2 cur = gq[m];
;                     const u32x2 q1 = dpp_prev<1>(cur, cur), q2 = dpp_prev<2>(cur, cur);
;                     float g0[4], g1[4], g2[4]; unpk4(cur, g0); unpk4(q1, g1); unpk4(q2, g2);
; #pragma unroll
;                     for (int j = 0; j < 4; ++j) { const float x1 = c1[m][j], x0 = c0[m][j];
;                         if (i < 1) g1[j] = x1;
;                         if (i < 2) g2[j] = (i == 1) ? x1 : x0; }
;                     finish(g0, g1, g2, w0, w1, w2, bb, acc[0][bj][m][hv], rs8[0][m], H + (size_t)row * 2816 + col); }
	v_lshlrev_b32_e32 v160, 16, v150
	v_pk_mul_f32 v[172:173], v[168:169], s[30:31] op_sel_hi:[1,0]
	v_mov_b32_dpp v187, v165 row_shr:2 row_mask:0xf bank_mask:0xf
	v_med3_f32 v172, v172, s47, v225
	v_med3_f32 v173, v173, s47, v225
	v_pk_mul_f32 v[174:175], v[172:173], v[172:173]
	v_pk_mul_f32 v[168:169], v[168:169], 0.5 op_sel_hi:[1,0]
	v_pk_fma_f32 v[176:177], v[174:175], s[34:35], v[148:149] op_sel_hi:[1,0,0] neg_lo:[1,0,0] neg_hi:[1,0,0]
	v_lshlrev_b32_e32 v211, 16, v187
	v_pk_fma_f32 v[176:177], v[174:175], v[176:177], s[38:39] op_sel_hi:[1,1,0]
	v_and_b32_e32 v187, 0xffff0000, v187
	v_pk_fma_f32 v[176:177], v[174:175], v[176:177], s[40:41] op_sel_hi:[1,1,0]
	v_cndmask_b32_e64 v171, v187, v171, s[8:9]
	v_pk_fma_f32 v[176:177], v[174:175], v[176:177], s[42:43] op_sel_hi:[1,1,0]
	v_cndmask_b32_e64 v170, v211, v170, s[8:9]
	v_pk_fma_f32 v[176:177], v[174:175], v[176:177], s[44:45] op_sel_hi:[1,1,0]
	v_pk_fma_f32 v[170:171], v[142:143], v[170:171], v[146:147]
	v_pk_fma_f32 v[176:177], v[174:175], v[176:177], s[46:47] op_sel_hi:[1,1,0]
	v_pk_fma_f32 v[170:171], v[138:139], v[228:229], v[170:171]
	v_pk_fma_f32 v[174:175], v[174:175], v[176:177], s[48:49] op_sel_hi:[1,1,0]
	v_mov_b32_dpp v176, v162 row_ror:1 row_mask:0xf bank_mask:0xf bound_ctrl:1
	v_pk_mul_f32 v[172:173], v[172:173], v[174:175]
	v_mov_b32_dpp v177, v163 row_ror:1 row_mask:0xf bank_mask:0xf bound_ctrl:1
	v_pk_fma_f32 v[168:169], v[168:169], v[172:173], v[168:169]
	v_mov_b32_dpp v176, v162 row_shr:1 row_mask:0xf bank_mask:0xf
	v_mul_f32_e32 v164, v60, v168
	v_mul_f32_e32 v174, v188, v164
	v_mul_f32_e32 v164, v61, v169
	v_mul_f32_e32 v175, v188, v164
	v_lshlrev_b32_e32 v164, 16, v165
	v_and_b32_e32 v165, 0xffff0000, v165
	v_pk_fma_f32 v[164:165], v[134:135], v[164:165], v[170:171]
	v_mov_b32_dpp v177, v163 row_shr:1 row_mask:0xf bank_mask:0xf
	v_pk_mul_f32 v[168:169], v[164:165], s[30:31] op_sel_hi:[1,0]
	v_pk_mul_f32 v[164:165], v[164:165], 0.5 op_sel_hi:[1,0]
	v_med3_f32 v168, v168, s47, v225
	v_med3_f32 v169, v169, s47, v225
	v_pk_mul_f32 v[170:171], v[168:169], v[168:169]
	v_and_b32_e32 v161, 0xffff0000, v150
	v_pk_fma_f32 v[172:173], v[170:171], s[34:35], v[148:149] op_sel_hi:[1,0,0] neg_lo:[1,0,0] neg_hi:[1,0,0]
	s_nop 0
	v_pk_fma_f32 v[172:173], v[170:171], v[172:173], s[38:39] op_sel_hi:[1,1,0]
	s_nop 0
	v_pk_fma_f32 v[172:173], v[170:171], v[172:173], s[40:41] op_sel_hi:[1,1,0]
	s_nop 0
	v_pk_fma_f32 v[172:173], v[170:171], v[172:173], s[42:43] op_sel_hi:[1,1,0]
	s_nop 0
	v_pk_fma_f32 v[172:173], v[170:171], v[172:173], s[44:45] op_sel_hi:[1,1,0]
	s_nop 0
	v_pk_fma_f32 v[172:173], v[170:171], v[172:173], s[46:47] op_sel_hi:[1,1,0]
	s_nop 0
	v_pk_fma_f32 v[170:171], v[170:171], v[172:173], s[48:49] op_sel_hi:[1,1,0]
	s_nop 0
	v_pk_mul_f32 v[168:169], v[168:169], v[170:171]
	s_nop 0
	v_pk_fma_f32 v[164:165], v[164:165], v[168:169], v[164:165]
	s_nop 0
	v_mul_f32_e32 v164, v62, v164
	v_mul_f32_e32 v168, v188, v164
	v_mul_f32_e32 v164, v63, v165
	v_mul_f32_e32 v165, v188, v164
	v_cvt_pk_bf16_f32 v164, v174, v175
	v_cvt_pk_bf16_f32 v165, v168, v165
	global_store_dwordx2 v[152:153], v[164:165], off sc1
	v_mov_b32_dpp v153, v227 row_ror:1 row_mask:0xf bank_mask:0xf bound_ctrl:1
	v_mov_b32_dpp v164, v226 row_ror:2 row_mask:0xf bank_mask:0xf bound_ctrl:1
	v_mov_b32_dpp v165, v227 row_ror:2 row_mask:0xf bank_mask:0xf bound_ctrl:1
	v_mov_b32_dpp v153, v227 row_shr:1 row_mask:0xf bank_mask:0xf
	v_mov_b32_dpp v152, v226 row_ror:1 row_mask:0xf bank_mask:0xf bound_ctrl:1
	v_mov_b32_dpp v164, v226 row_shr:2 row_mask:0xf bank_mask:0xf
	v_mov_b32_dpp v165, v227 row_shr:2 row_mask:0xf bank_mask:0xf
	v_and_b32_e32 v170, 0xffff0000, v153
	v_mov_b32_dpp v152, v226 row_shr:1 row_mask:0xf bank_mask:0xf
	v_lshlrev_b32_e32 v172, 16, v164
	v_and_b32_e32 v171, 0xffff0000, v164
	v_lshlrev_b32_e32 v173, 16, v165
	v_and_b32_e32 v174, 0xffff0000, v165
	s_waitcnt vmcnt(1)
	v_cndmask_b32_e64 v165, v170, v215, s[0:1]
	v_cndmask_b32_e32 v170, v178, v212, vcc
	v_cndmask_b32_e32 v175, v179, v213, vcc
	v_lshlrev_b32_e32 v168, 16, v152
	v_and_b32_e32 v152, 0xffff0000, v152
	v_lshlrev_b32_e32 v169, 16, v153
	v_cndmask_b32_e64 v171, v171, v175, s[8:9]
	v_cndmask_b32_e64 v170, v172, v170, s[8:9]
	v_cndmask_b32_e64 v153, v152, v213, s[0:1]
	v_cndmask_b32_e64 v152, v168, v212, s[0:1]
	v_cndmask_b32_e64 v164, v169, v214, s[0:1]
	v_cndmask_b32_e32 v168, v180, v214, vcc
	v_cndmask_b32_e32 v169, v181, v215, vcc
	v_pk_fma_f32 v[170:171], v[140:141], v[170:171], v[144:145]
	v_cndmask_b32_e64 v169, v174, v169, s[8:9]
	v_cndmask_b32_e64 v168, v173, v168, s[8:9]
	v_lshlrev_b32_e32 v172, 16, v226
	v_and_b32_e32 v173, 0xffff0000, v226
	v_pk_fma_f32 v[152:153], v[136:137], v[152:153], v[170:171]
	v_pk_fma_f32 v[168:169], v[142:143], v[168:169], v[146:147]
	v_pk_fma_f32 v[152:153], v[132:133], v[172:173], v[152:153]
	v_pk_fma_f32 v[164:165], v[138:139], v[164:165], v[168:169]
	v_pk_mul_f32 v[168:169], v[152:153], s[30:31] op_sel_hi:[1,0]
	v_pk_mul_f32 v[152:153], v[152:153], 0.5 op_sel_hi:[1,0]
	v_med3_f32 v168, v168, s47, v225
	v_med3_f32 v169, v169, s47, v225
	v_pk_mul_f32 v[170:171], v[168:169], v[168:169]
	v_mov_b32_dpp v178, v162 row_ror:2 row_mask:0xf bank_mask:0xf bound_ctrl:1
	v_pk_fma_f32 v[172:173], v[170:171], s[34:35], v[148:149] op_sel_hi:[1,0,0] neg_lo:[1,0,0] neg_hi:[1,0,0]
	v_mov_b32_dpp v179, v163 row_ror:2 row_mask:0xf bank_mask:0xf bound_ctrl:1
	v_pk_fma_f32 v[172:173], v[170:171], v[172:173], s[38:39] op_sel_hi:[1,1,0]
	v_mov_b32_dpp v178, v162 row_shr:2 row_mask:0xf bank_mask:0xf
	v_pk_fma_f32 v[172:173], v[170:171], v[172:173], s[40:41] op_sel_hi:[1,1,0]
	v_mov_b32_dpp v179, v163 row_shr:2 row_mask:0xf bank_mask:0xf
; __device__ __forceinline__ unsigned cvt_pk_bf16(float lo, float hi) { unsigned r; asm volatile("v_cvt_pk_bf16_f32 %0, %1, %2" : "=v"(r) : "v"(lo), "v"(hi)); return r; }
;     static __device__ __forceinline__ void unpk4(const u32x2 w, float (&o)[4]) { o[0] = bf_lo(w.x); o[1] = bf_hi(w.x); o[2] = bf_lo(w.y); o[3] = bf_hi(w.y); }
;     template <int N> static __device__ __forceinline__ u32x2 dpp_prev(const u32x2 pv, const u32x2 cur) { u32x2 r; r.x = dpp_prev1<N>(pv.x, cur.x); r.y = dpp_prev1<N>(pv.y, cur.y); return r; }
;     static __device__ __forceinline__ void finish(const float (&g0)[4], const float (&g1)[4], const float (&g2)[4], const float (&w0)[4], const float (&w1)[4], const float (&w2)[4], const float (&bb)[4],
;                                                   const f32x4 v, float rs, bf16_t* dst) {
;         float h[4];
; #pragma unroll
;         for (int j = 0; j < 4; j += 2) {
;             const f32x2 gc = (f32x2){bb[j] + w0[j] * g2[j] + w1[j] * g1[j] + w2[j] * g0[j], bb[j + 1] + w0[j + 1] * g2[j + 1] + w1[j + 1] * g1[j + 1] + w2[j + 1] * g0[j + 1]};
;             const f32x2 ge = gelu_pk(gc); h[j] = ge.x * v[j] * rs; h[j + 1] = ge.y * v[j + 1] * rs; }
;         u32x2 w; w.x = cvt_pk_bf16(h[0], h[1]); w.y = cvt_pk_bf16(h[2], h[3]);
;         *(u32x2*)dst = w;
;     }
;     __device__ __forceinline__ void operator()(const f32x4 (&acc)[2][2][4][2], const Unit& u, int wr, int wc, int fr, int fq) const {
;     ...
;                 for (int m = mh; m < mh + 2; ++m) { const int row = row0 + m * 16; const float* cx = ctx + (size_t)((row - 32768) >> 3) * 2 * 2816 + col;
;                     c0[m] = *(const f32x4*)cx; c1[m] = *(const f32x4*)(cx + 2816); }
; #pragma unroll
;                 for (int m = mh; m < mh + 2; ++m) { const int row = row0 + m * 16; const u32x2 cur = gq[m];
;                     const u32x2 q1 = dpp_prev<1>(cur, cur), q2 = dpp_prev<2>(cur, cur);
;                     float g0[4], g1[4], g2[4]; unpk4(cur, g0); unpk4(q1, g1); unpk4(q2, g2);
; #pragma unroll
;                     for (int j = 0; j < 4; ++j) { const float x1 = c1[m][j], x0 = c0[m][j];
;                         if (i < 1) g1[j] = x1;
;                         if (i < 2) g2[j] = (i == 1) ? x1 : x0; }
;                     finish(g0, g1, g2, w0, w1, w2, bb, acc[0][bj][m][hv], rs8[0][m], H + (size_t)row * 2816 + col); }
	v_pk_fma_f32 v[172:173], v[170:171], v[172:173], s[42:43] op_sel_hi:[1,1,0]
	v_lshlrev_b32_e32 v180, 16, v176
	v_pk_fma_f32 v[172:173], v[170:171], v[172:173], s[44:45] op_sel_hi:[1,1,0]
	v_and_b32_e32 v176, 0xffff0000, v176
	v_pk_fma_f32 v[172:173], v[170:171], v[172:173], s[46:47] op_sel_hi:[1,1,0]
	v_lshlrev_b32_e32 v181, 16, v177
	v_pk_fma_f32 v[170:171], v[170:171], v[172:173], s[48:49] op_sel_hi:[1,1,0]
	v_and_b32_e32 v185, 0xffff0000, v178
	v_pk_mul_f32 v[168:169], v[168:169], v[170:171]
	v_lshlrev_b32_e32 v187, 16, v179
	v_pk_fma_f32 v[152:153], v[152:153], v[168:169], v[152:153]
	v_and_b32_e32 v189, 0xffff0000, v179
	v_mul_f32_e32 v152, v52, v152
	v_mul_f32_e32 v172, v186, v152
	v_mul_f32_e32 v152, v53, v153
	v_mul_f32_e32 v173, v186, v152
	v_lshlrev_b32_e32 v152, 16, v227
	v_and_b32_e32 v153, 0xffff0000, v227
	v_pk_fma_f32 v[152:153], v[134:135], v[152:153], v[164:165]
	s_nop 0
	v_pk_mul_f32 v[164:165], v[152:153], s[30:31] op_sel_hi:[1,0]
	v_pk_mul_f32 v[152:153], v[152:153], 0.5 op_sel_hi:[1,0]
	v_med3_f32 v164, v164, s47, v225
	v_med3_f32 v165, v165, s47, v225
	v_pk_mul_f32 v[168:169], v[164:165], v[164:165]
	s_nop 0
	v_pk_fma_f32 v[170:171], v[168:169], s[34:35], v[148:149] op_sel_hi:[1,0,0] neg_lo:[1,0,0] neg_hi:[1,0,0]
	s_nop 0
	v_pk_fma_f32 v[170:171], v[168:169], v[170:171], s[38:39] op_sel_hi:[1,1,0]
	s_nop 0
	v_pk_fma_f32 v[170:171], v[168:169], v[170:171], s[40:41] op_sel_hi:[1,1,0]
	s_nop 0
	v_pk_fma_f32 v[170:171], v[168:169], v[170:171], s[42:43] op_sel_hi:[1,1,0]
	s_nop 0
	v_pk_fma_f32 v[170:171], v[168:169], v[170:171], s[44:45] op_sel_hi:[1,1,0]
	s_nop 0
	v_pk_fma_f32 v[170:171], v[168:169], v[170:171], s[46:47] op_sel_hi:[1,1,0]
	s_nop 0
	v_pk_fma_f32 v[168:169], v[168:169], v[170:171], s[48:49] op_sel_hi:[1,1,0]
	s_nop 0
	v_pk_mul_f32 v[164:165], v[164:165], v[168:169]
	s_nop 0
	v_pk_fma_f32 v[152:153], v[152:153], v[164:165], v[152:153]
	s_nop 0
	v_mul_f32_e32 v152, v54, v152
	v_mul_f32_e32 v164, v186, v152
	v_mul_f32_e32 v152, v55, v153
	v_mul_f32_e32 v153, v186, v152
	v_cvt_pk_bf16_f32 v152, v172, v173
	v_cvt_pk_bf16_f32 v153, v164, v153
	v_mad_i64_i32 v[164:165], s[10:11], v166, s45, v[182:183]
	global_store_dwordx2 v[154:155], v[152:153], off sc1
	v_add_co_u32_e64 v152, s[10:11], s41, v164
	s_nop 1
	v_addc_co_u32_e64 v153, s[10:11], 0, v165, s[10:11]
	global_load_dwordx4 v[152:155], v[152:153], off offset:3072
	s_nop 0
	global_load_dwordx4 v[168:171], v[164:165], off
	v_mad_i64_i32 v[164:165], s[10:11], v167, s45, v[182:183]
	v_add_co_u32_e64 v172, s[10:11], s41, v164
	v_and_b32_e32 v182, 0xffff0000, v177
	s_nop 0
	v_addc_co_u32_e64 v173, s[10:11], 0, v165, s[10:11]
	global_load_dwordx4 v[164:167], v[164:165], off
	s_nop 0
	global_load_dwordx4 v[172:175], v[172:173], off offset:3072
	v_lshlrev_b32_e32 v183, 16, v178
	s_waitcnt vmcnt(3)
	v_cndmask_b32_e64 v177, v176, v153, s[0:1]
	s_waitcnt vmcnt(2)
	v_cndmask_b32_e32 v168, v168, v152, vcc
	v_cndmask_b32_e32 v169, v169, v153, vcc
	v_cndmask_b32_e64 v176, v180, v152, s[0:1]
	v_cndmask_b32_e64 v179, v182, v155, s[0:1]
	v_cndmask_b32_e64 v178, v181, v154, s[0:1]
	v_cndmask_b32_e32 v152, v170, v154, vcc
	v_cndmask_b32_e32 v153, v171, v155, vcc
	v_cndmask_b32_e64 v155, v185, v169, s[8:9]
	v_cndmask_b32_e64 v154, v183, v168, s[8:9]
	v_pk_fma_f32 v[154:155], v[140:141], v[154:155], v[144:145]
	v_lshlrev_b32_e32 v168, 16, v162
	v_and_b32_e32 v169, 0xffff0000, v162
	v_pk_fma_f32 v[154:155], v[136:137], v[176:177], v[154:155]
	v_cndmask_b32_e64 v153, v189, v153, s[8:9]
	v_pk_fma_f32 v[154:155], v[132:133], v[168:169], v[154:155]
	v_cndmask_b32_e64 v152, v187, v152, s[8:9]
	v_pk_mul_f32 v[168:169], v[154:155], s[30:31] op_sel_hi:[1,0]
	v_pk_mul_f32 v[154:155], v[154:155], 0.5 op_sel_hi:[1,0]
	v_med3_f32 v168, v168, s47, v225
	v_med3_f32 v169, v169, s47, v225
	v_pk_mul_f32 v[170:171], v[168:169], v[168:169]
	v_pk_fma_f32 v[152:153], v[142:143], v[152:153], v[146:147]
	v_pk_fma_f32 v[176:177], v[170:171], s[34:35], v[148:149] op_sel_hi:[1,0,0] neg_lo:[1,0,0] neg_hi:[1,0,0]
	v_pk_fma_f32 v[152:153], v[138:139], v[178:179], v[152:153]
	v_pk_fma_f32 v[176:177], v[170:171], v[176:177], s[38:39] op_sel_hi:[1,1,0]
	s_nop 0
	v_pk_fma_f32 v[176:177], v[170:171], v[176:177], s[40:41] op_sel_hi:[1,1,0]
	s_nop 0
	v_pk_fma_f32 v[176:177], v[170:171], v[176:177], s[42:43] op_sel_hi:[1,1,0]
	s_nop 0
	v_pk_fma_f32 v[176:177], v[170:171], v[176:177], s[44:45] op_sel_hi:[1,1,0]
	s_nop 0
	v_pk_fma_f32 v[176:177], v[170:171], v[176:177], s[46:47] op_sel_hi:[1,1,0]
	s_nop 0
	v_pk_fma_f32 v[170:171], v[170:171], v[176:177], s[48:49] op_sel_hi:[1,1,0]
	s_nop 0
	v_pk_mul_f32 v[168:169], v[168:169], v[170:171]
	s_nop 0
	v_pk_fma_f32 v[154:155], v[154:155], v[168:169], v[154:155]
	s_nop 0
	v_mul_f32_e32 v154, v44, v154
	v_mul_f32_e32 v170, v184, v154
	v_mul_f32_e32 v154, v45, v155
	v_mul_f32_e32 v171, v184, v154
	v_lshlrev_b32_e32 v154, 16, v163
	v_and_b32_e32 v155, 0xffff0000, v163
	v_pk_fma_f32 v[152:153], v[134:135], v[154:155], v[152:153]
	s_nop 0
	v_pk_mul_f32 v[154:155], v[152:153], s[30:31] op_sel_hi:[1,0]
	v_pk_mul_f32 v[152:153], v[152:153], 0.5 op_sel_hi:[1,0]
	v_med3_f32 v154, v154, s47, v225
	v_med3_f32 v155, v155, s47, v225
	v_pk_mul_f32 v[162:163], v[154:155], v[154:155]
	s_nop 0
	v_pk_fma_f32 v[168:169], v[162:163], s[34:35], v[148:149] op_sel_hi:[1,0,0] neg_lo:[1,0,0] neg_hi:[1,0,0]
	s_nop 0
	v_pk_fma_f32 v[168:169], v[162:163], v[168:169], s[38:39] op_sel_hi:[1,1,0]
	s_nop 0
	v_pk_fma_f32 v[168:169], v[162:163], v[168:169], s[40:41] op_sel_hi:[1,1,0]
	s_nop 0
	v_pk_fma_f32 v[168:169], v[162:163], v[168:169], s[42:43] op_sel_hi:[1,1,0]
	s_nop 0
	v_pk_fma_f32 v[168:169], v[162:163], v[168:169], s[44:45] op_sel_hi:[1,1,0]
	s_nop 0
	v_pk_fma_f32 v[168:169], v[162:163], v[168:169], s[46:47] op_sel_hi:[1,1,0]
	s_nop 0
	v_pk_fma_f32 v[162:163], v[162:163], v[168:169], s[48:49] op_sel_hi:[1,1,0]
	s_nop 0
	v_pk_mul_f32 v[154:155], v[154:155], v[162:163]
	s_nop 0
	v_pk_fma_f32 v[152:153], v[152:153], v[154:155], v[152:153]
	v_mov_b32_dpp v155, v151 row_ror:2 row_mask:0xf bank_mask:0xf bound_ctrl:1
	v_mul_f32_e32 v152, v46, v152
	v_mul_f32_e32 v154, v184, v152
	v_mul_f32_e32 v152, v47, v153
	v_mul_f32_e32 v153, v184, v152
	v_cvt_pk_bf16_f32 v152, v170, v171
	v_cvt_pk_bf16_f32 v153, v154, v153
	global_store_dwordx2 v[156:157], v[152:153], off sc1
	v_mov_b32_dpp v154, v150 row_ror:2 row_mask:0xf bank_mask:0xf bound_ctrl:1
	v_mov_b32_dpp v153, v151 row_ror:1 row_mask:0xf bank_mask:0xf bound_ctrl:1
	v_mov_b32_dpp v152, v150 row_ror:1 row_mask:0xf bank_mask:0xf bound_ctrl:1
	v_mov_b32_dpp v154, v150 row_shr:2 row_mask:0xf bank_mask:0xf
	v_mov_b32_dpp v153, v151 row_shr:1 row_mask:0xf bank_mask:0xf
	v_mov_b32_dpp v155, v151 row_shr:2 row_mask:0xf bank_mask:0xf
	v_and_b32_e32 v162, 0xffff0000, v153
	v_mov_b32_dpp v152, v150 row_shr:1 row_mask:0xf bank_mask:0xf
	v_lshlrev_b32_e32 v168, 16, v154
	v_and_b32_e32 v163, 0xffff0000, v154
	v_lshlrev_b32_e32 v169, 16, v155
	v_and_b32_e32 v170, 0xffff0000, v155
	s_waitcnt vmcnt(1)
; __device__ __forceinline__ unsigned cvt_pk_bf16(float lo, float hi) { unsigned r; asm volatile("v_cvt_pk_bf16_f32 %0, %1, %2" : "=v"(r) : "v"(lo), "v"(hi)); return r; }
;     static __device__ __forceinline__ void unpk4(const u32x2 w, float (&o)[4]) { o[0] = bf_lo(w.x); o[1] = bf_hi(w.x); o[2] = bf_lo(w.y); o[3] = bf_hi(w.y); }
;     template <int N> static __device__ __forceinline__ u32x2 dpp_prev(const u32x2 pv, const u32x2 cur) { u32x2 r; r.x = dpp_prev1<N>(pv.x, cur.x); r.y = dpp_prev1<N>(pv.y, cur.y); return r; }
;     static __device__ __forceinline__ void finish(const float (&g0)[4], const float (&g1)[4], const float (&g2)[4], const float (&w0)[4], const float (&w1)[4], const float (&w2)[4], const float (&bb)[4],
;                                                   const f32x4 v, float rs, bf16_t* dst) {
;         float h[4];
; #pragma unroll
;         for (int j = 0; j < 4; j += 2) {
;             const f32x2 gc = (f32x2){bb[j] + w0[j] * g2[j] + w1[j] * g1[j] + w2[j] * g0[j], bb[j + 1] + w0[j + 1] * g2[j + 1] + w1[j + 1] * g1[j + 1] + w2[j + 1] * g0[j + 1]};
;             const f32x2 ge = gelu_pk(gc); h[j] = ge.x * v[j] * rs; h[j + 1] = ge.y * v[j + 1] * rs; }
;         u32x2 w; w.x = cvt_pk_bf16(h[0], h[1]); w.y = cvt_pk_bf16(h[2], h[3]);
;         *(u32x2*)dst = w;
;     }
;     __device__ __forceinline__ void operator()(const f32x4 (&acc)[2][2][4][2], const Unit& u, int wr, int wc, int fr, int fq) const {
;     ...
;                 for (int m = mh; m < mh + 2; ++m) { const int row = row0 + m * 16; const float* cx = ctx + (size_t)((row - 32768) >> 3) * 2 * 2816 + col;
;                     c0[m] = *(const f32x4*)cx; c1[m] = *(const f32x4*)(cx + 2816); }
; #pragma unroll
;                 for (int m = mh; m < mh + 2; ++m) { const int row = row0 + m * 16; const u32x2 cur = gq[m];
;                     const u32x2 q1 = dpp_prev<1>(cur, cur), q2 = dpp_prev<2>(cur, cur);
;                     float g0[4], g1[4], g2[4]; unpk4(cur, g0); unpk4(q1, g1); unpk4(q2, g2);
; #pragma unroll
;                     for (int j = 0; j < 4; ++j) { const float x1 = c1[m][j], x0 = c0[m][j];
;                         if (i < 1) g1[j] = x1;
;                         if (i < 2) g2[j] = (i == 1) ? x1 : x0; }
;                     finish(g0, g1, g2, w0, w1, w2, bb, acc[0][bj][m][hv], rs8[0][m], H + (size_t)row * 2816 + col); }
	v_cndmask_b32_e64 v155, v162, v175, s[0:1]
	v_cndmask_b32_e32 v162, v164, v172, vcc
	v_cndmask_b32_e32 v164, v165, v173, vcc
	v_lshlrev_b32_e32 v156, 16, v152
	v_and_b32_e32 v152, 0xffff0000, v152
	v_cndmask_b32_e64 v163, v163, v164, s[8:9]
	v_cndmask_b32_e64 v162, v168, v162, s[8:9]
	v_lshlrev_b32_e32 v157, 16, v153
	v_cndmask_b32_e64 v153, v152, v173, s[0:1]
	v_cndmask_b32_e64 v152, v156, v172, s[0:1]
	v_pk_fma_f32 v[140:141], v[140:141], v[162:163], v[144:145]
	v_cndmask_b32_e64 v154, v157, v174, s[0:1]
	v_pk_fma_f32 v[136:137], v[136:137], v[152:153], v[140:141]
	v_cndmask_b32_e32 v156, v166, v174, vcc
	v_pk_fma_f32 v[132:133], v[132:133], v[160:161], v[136:137]
	v_cndmask_b32_e32 v157, v167, v175, vcc
	v_pk_mul_f32 v[136:137], v[132:133], s[30:31] op_sel_hi:[1,0]
	v_cndmask_b32_e64 v157, v170, v157, s[8:9]
	v_cndmask_b32_e64 v156, v169, v156, s[8:9]
	v_med3_f32 v136, v136, s47, v225
	v_med3_f32 v137, v137, s47, v225
	v_pk_fma_f32 v[142:143], v[142:143], v[156:157], v[146:147]
	v_pk_mul_f32 v[140:141], v[136:137], v[136:137]
	v_pk_fma_f32 v[138:139], v[138:139], v[154:155], v[142:143]
	v_pk_fma_f32 v[142:143], v[140:141], s[34:35], v[148:149] op_sel_hi:[1,0,0] neg_lo:[1,0,0] neg_hi:[1,0,0]
	v_pk_mul_f32 v[132:133], v[132:133], 0.5 op_sel_hi:[1,0]
	v_pk_fma_f32 v[142:143], v[140:141], v[142:143], s[38:39] op_sel_hi:[1,1,0]
	s_mov_b64 s[0:1], 0
	v_pk_fma_f32 v[142:143], v[140:141], v[142:143], s[40:41] op_sel_hi:[1,1,0]
	s_nop 0
	v_pk_fma_f32 v[142:143], v[140:141], v[142:143], s[42:43] op_sel_hi:[1,1,0]
	s_nop 0
	v_pk_fma_f32 v[142:143], v[140:141], v[142:143], s[44:45] op_sel_hi:[1,1,0]
	s_nop 0
	v_pk_fma_f32 v[142:143], v[140:141], v[142:143], s[46:47] op_sel_hi:[1,1,0]
	s_nop 0
	v_pk_fma_f32 v[140:141], v[140:141], v[142:143], s[48:49] op_sel_hi:[1,1,0]
	s_nop 0
	v_pk_mul_f32 v[136:137], v[136:137], v[140:141]
	s_nop 0
	v_pk_fma_f32 v[132:133], v[132:133], v[136:137], v[132:133]
	s_nop 0
	v_mul_f32_e32 v132, v36, v132
	v_mul_f32_e32 v140, v2, v132
	v_mul_f32_e32 v132, v37, v133
	v_mul_f32_e32 v141, v2, v132
	v_lshlrev_b32_e32 v132, 16, v151
	v_and_b32_e32 v133, 0xffff0000, v151
	v_pk_fma_f32 v[132:133], v[134:135], v[132:133], v[138:139]
	s_nop 0
	v_pk_mul_f32 v[134:135], v[132:133], s[30:31] op_sel_hi:[1,0]
	v_pk_mul_f32 v[132:133], v[132:133], 0.5 op_sel_hi:[1,0]
	v_med3_f32 v134, v134, s47, v225
	v_med3_f32 v135, v135, s47, v225
	v_pk_mul_f32 v[136:137], v[134:135], v[134:135]
	s_nop 0
	v_pk_fma_f32 v[138:139], v[136:137], s[34:35], v[148:149] op_sel_hi:[1,0,0] neg_lo:[1,0,0] neg_hi:[1,0,0]
	s_nop 0
	v_pk_fma_f32 v[138:139], v[136:137], v[138:139], s[38:39] op_sel_hi:[1,1,0]
	s_nop 0
	v_pk_fma_f32 v[138:139], v[136:137], v[138:139], s[40:41] op_sel_hi:[1,1,0]
	s_nop 0
	v_pk_fma_f32 v[138:139], v[136:137], v[138:139], s[42:43] op_sel_hi:[1,1,0]
	s_nop 0
	v_pk_fma_f32 v[138:139], v[136:137], v[138:139], s[44:45] op_sel_hi:[1,1,0]
	s_nop 0
	v_pk_fma_f32 v[138:139], v[136:137], v[138:139], s[46:47] op_sel_hi:[1,1,0]
	s_nop 0
	v_pk_fma_f32 v[136:137], v[136:137], v[138:139], s[48:49] op_sel_hi:[1,1,0]
	s_nop 0
	v_pk_mul_f32 v[134:135], v[134:135], v[136:137]
	s_nop 0
	v_pk_fma_f32 v[132:133], v[132:133], v[134:135], v[132:133]
	s_nop 0
	v_mul_f32_e32 v132, v38, v132
	v_mul_f32_e32 v134, v2, v132
	v_mul_f32_e32 v132, v39, v133
	v_mul_f32_e32 v133, v2, v132
	v_cvt_pk_bf16_f32 v132, v140, v141
	v_cvt_pk_bf16_f32 v133, v134, v133
	global_store_dwordx2 v[158:159], v[132:133], off sc1

; __device__ __forceinline__ unsigned cvt_pk_bf16(float lo, float hi) { unsigned r; asm volatile("v_cvt_pk_bf16_f32 %0, %1, %2" : "=v"(r) : "v"(lo), "v"(hi)); return r; }
;     static __device__ __forceinline__ u32x2 finish2(const float (&g0)[4], const float (&g1)[4], const float (&g2)[4], const float (&w0)[4], const float (&w1)[4], const float (&w2)[4], const float (&bb)[4],
;                                                     const f32x4 v, float rs) {
;         float h[4];
; #pragma unroll
;         for (int j = 0; j < 4; j += 2) {
;             const f32x2 gc = (f32x2){bb[j] + w0[j] * g2[j] + w1[j] * g1[j] + w2[j] * g0[j], bb[j + 1] + w0[j + 1] * g2[j + 1] + w1[j + 1] * g1[j + 1] + w2[j + 1] * g0[j + 1]};
;             const f32x2 ge = gelu_pk(gc) * ((f32x2){v[j], v[j + 1]} * rs); h[j] = ge.x; h[j + 1] = ge.y; }
;         u32x2 w; w.x = cvt_pk_bf16(h[0], h[1]); w.y = cvt_pk_bf16(h[2], h[3]); return w;
;     }
;     __device__ __forceinline__ void operator()(const f32x4 (&acc)[2][2][4][2], const Unit& u, int wr, int wc, int fr, int fq) const {
;     ...
;             for (int ai = 0; ai < 2; ++ai) { const int R0 = u.rb + ai * HALF + wr * 64; const bf16_t* gp = G + (size_t)(R0 + fr) * 2816 + col8;
;                 u32x4 gq[4], prv = (u32x4){0u, 0u, 0u, 0u};
; #pragma unroll
;                 for (int m = 0; m < 4; ++m) gq[m] = *(const u32x4*)(gp + (size_t)m * 16 * 2816);
;                 if ((R0 & 8191) != 0) prv = *(const u32x4*)(gp - (size_t)16 * 2816);
;                 u32x4 pv = prv;
; #pragma unroll
;                 for (int m = 0; m < 4; ++m) { const u32x4 cur = gq[m]; u32x4 hw;
; #pragma unroll
;                     for (int hv = 0; hv < 2; ++hv) { const u32x2 c2 = half2(cur, hv), p2 = half2(pv, hv);
;                         const u32x2 q1 = dpp_prev<1>(p2, c2), q2 = dpp_prev<2>(p2, c2);
;                         float g0[4], g1[4], g2[4]; unpk4(c2, g0); unpk4(q1, g1); unpk4(q2, g2);
;                         const u32x2 r = finish2(g0, g1, g2, w0[hv], w1[hv], w2[hv], bb[hv], acc[ai][bj][m][hv], rs8[ai][m]);
;                         if (hv == 0) { hw.x = r.x; hw.y = r.y; } else { hw.z = r.x; hw.w = r.y; } }
;                     *(u32x4*)(H + (size_t)(R0 + fr + 16 * m) * 2816 + col8) = hw;
;                     pv = cur; } }
.LBB0_1013:
	s_waitcnt vmcnt(0)
	v_mov_b32_dpp v195, v180 row_ror:2 row_mask:0xf bank_mask:0xf bound_ctrl:1
	v_mov_b32_dpp v191, v180 row_ror:1 row_mask:0xf bank_mask:0xf bound_ctrl:1
	v_mad_i64_i32 v[230:231], s[8:9], v210, s91, 0
	v_mov_b32_dpp v195, v176 row_shr:2 row_mask:0xf bank_mask:0xf
	v_mov_b32_dpp v191, v176 row_shr:1 row_mask:0xf bank_mask:0xf
	v_lshlrev_b32_e32 v210, 16, v195
	v_and_b32_e32 v211, 0xffff0000, v195
	v_mov_b32_dpp v193, v181 row_ror:1 row_mask:0xf bank_mask:0xf bound_ctrl:1
	v_mov_b32_dpp v229, v181 row_ror:2 row_mask:0xf bank_mask:0xf bound_ctrl:1
	v_lshlrev_b32_e32 v180, 16, v191
	v_and_b32_e32 v181, 0xffff0000, v191
	v_pk_fma_f32 v[210:211], v[148:149], v[210:211], v[160:161]
	v_lshlrev_b32_e32 v232, 16, v176
	v_and_b32_e32 v233, 0xffff0000, v176
	v_pk_fma_f32 v[180:181], v[152:153], v[180:181], v[210:211]
	v_mov_b32_dpp v229, v177 row_shr:2 row_mask:0xf bank_mask:0xf
	v_pk_fma_f32 v[180:181], v[156:157], v[232:233], v[180:181]
	v_mov_b32_dpp v193, v177 row_shr:1 row_mask:0xf bank_mask:0xf
	v_pk_mul_f32 v[210:211], v[180:181], s[30:31] op_sel_hi:[1,0]
	v_lshlrev_b32_e32 v228, 16, v229
	v_med3_f32 v232, v210, s47, v225
	v_med3_f32 v233, v211, s47, v225
	v_pk_mul_f32 v[234:235], v[232:233], v[232:233]
	v_mov_b64_e32 v[210:211], s[36:37]
	v_pk_fma_f32 v[236:237], v[234:235], s[34:35], v[210:211] op_sel_hi:[1,0,0] neg_lo:[1,0,0] neg_hi:[1,0,0]
	v_and_b32_e32 v229, 0xffff0000, v229
	v_pk_fma_f32 v[236:237], v[234:235], v[236:237], s[38:39] op_sel_hi:[1,1,0]
	v_pk_mul_f32 v[180:181], v[180:181], 0.5 op_sel_hi:[1,0]
	v_pk_fma_f32 v[236:237], v[234:235], v[236:237], s[40:41] op_sel_hi:[1,1,0]
	v_lshlrev_b32_e32 v226, 16, v193
	v_pk_fma_f32 v[236:237], v[234:235], v[236:237], s[42:43] op_sel_hi:[1,1,0]
	v_and_b32_e32 v227, 0xffff0000, v193
	v_pk_fma_f32 v[236:237], v[234:235], v[236:237], s[44:45] op_sel_hi:[1,1,0]
	v_pk_mul_f32 v[128:129], v[128:129], v[188:189] op_sel_hi:[1,0]
	v_pk_fma_f32 v[236:237], v[234:235], v[236:237], s[46:47] op_sel_hi:[1,1,0]
	v_pk_fma_f32 v[228:229], v[150:151], v[228:229], v[162:163]
	v_pk_fma_f32 v[234:235], v[234:235], v[236:237], s[48:49] op_sel_hi:[1,1,0]
	v_pk_fma_f32 v[226:227], v[154:155], v[226:227], v[228:229]
	v_pk_mul_f32 v[232:233], v[232:233], v[234:235]
	v_pk_mul_f32 v[130:131], v[130:131], v[188:189] op_sel_hi:[1,0]
	v_pk_fma_f32 v[180:181], v[180:181], v[232:233], v[180:181]
	v_pk_mul_f32 v[124:125], v[124:125], v[188:189] op_sel_hi:[1,0]
	v_pk_mul_f32 v[128:129], v[128:129], v[180:181]
	v_lshlrev_b32_e32 v180, 16, v177
	v_and_b32_e32 v181, 0xffff0000, v177
	v_pk_fma_f32 v[180:181], v[158:159], v[180:181], v[226:227]
	v_readlane_b32 s8, v240, 58
	v_pk_mul_f32 v[226:227], v[180:181], s[30:31] op_sel_hi:[1,0]
	v_pk_mul_f32 v[180:181], v[180:181], 0.5 op_sel_hi:[1,0]
	v_med3_f32 v226, v226, s47, v225
	v_med3_f32 v227, v227, s47, v225
	v_pk_mul_f32 v[228:229], v[226:227], v[226:227]
	v_readlane_b32 s9, v240, 59
	v_pk_fma_f32 v[232:233], v[228:229], s[34:35], v[210:211] op_sel_hi:[1,0,0] neg_lo:[1,0,0] neg_hi:[1,0,0]
	v_pk_mul_f32 v[126:127], v[126:127], v[188:189] op_sel_hi:[1,0]
	v_pk_fma_f32 v[232:233], v[228:229], v[232:233], s[38:39] op_sel_hi:[1,1,0]
	v_pk_mul_f32 v[120:121], v[120:121], v[186:187] op_sel_hi:[1,0]
	v_pk_fma_f32 v[232:233], v[228:229], v[232:233], s[40:41] op_sel_hi:[1,1,0]
	v_pk_mul_f32 v[122:123], v[122:123], v[186:187] op_sel_hi:[1,0]
	v_pk_fma_f32 v[232:233], v[228:229], v[232:233], s[42:43] op_sel_hi:[1,1,0]
	v_pk_mul_f32 v[116:117], v[116:117], v[186:187] op_sel_hi:[1,0]
	v_pk_fma_f32 v[232:233], v[228:229], v[232:233], s[44:45] op_sel_hi:[1,1,0]
	v_pk_mul_f32 v[118:119], v[118:119], v[186:187] op_sel_hi:[1,0]
	v_pk_fma_f32 v[232:233], v[228:229], v[232:233], s[46:47] op_sel_hi:[1,1,0]
	v_pk_mul_f32 v[112:113], v[112:113], v[184:185] op_sel_hi:[1,0]
	v_pk_fma_f32 v[228:229], v[228:229], v[232:233], s[48:49] op_sel_hi:[1,1,0]
	v_pk_mul_f32 v[114:115], v[114:115], v[184:185] op_sel_hi:[1,0]
	v_pk_mul_f32 v[226:227], v[226:227], v[228:229]
	v_lshlrev_b32_e32 v228, 16, v178
	v_pk_fma_f32 v[180:181], v[180:181], v[226:227], v[180:181]
	v_cvt_pk_bf16_f32 v226, v128, v129
	v_mov_b32_dpp v129, v182 row_ror:1 row_mask:0xf bank_mask:0xf bound_ctrl:1
	v_pk_mul_f32 v[130:131], v[130:131], v[180:181]
	v_mov_b32_dpp v181, v182 row_ror:2 row_mask:0xf bank_mask:0xf bound_ctrl:1
	v_mov_b32_dpp v129, v178 row_shr:1 row_mask:0xf bank_mask:0xf
	v_lshlrev_b32_e32 v128, 16, v129
	v_mov_b32_dpp v181, v178 row_shr:2 row_mask:0xf bank_mask:0xf
	v_lshlrev_b32_e32 v180, 16, v181
	v_and_b32_e32 v181, 0xffff0000, v181
	v_and_b32_e32 v129, 0xffff0000, v129
	v_pk_fma_f32 v[180:181], v[132:133], v[180:181], v[144:145]
	v_and_b32_e32 v229, 0xffff0000, v178
	v_pk_fma_f32 v[128:129], v[136:137], v[128:129], v[180:181]
	v_cvt_pk_bf16_f32 v227, v130, v131
	v_mov_b32_dpp v131, v183 row_ror:1 row_mask:0xf bank_mask:0xf bound_ctrl:1
	v_pk_fma_f32 v[128:129], v[140:141], v[228:229], v[128:129]
	v_mov_b32_dpp v183, v183 row_ror:2 row_mask:0xf bank_mask:0xf bound_ctrl:1
	v_pk_mul_f32 v[180:181], v[128:129], s[30:31] op_sel_hi:[1,0]
	v_mov_b32_dpp v131, v179 row_shr:1 row_mask:0xf bank_mask:0xf
	v_med3_f32 v180, v180, s47, v225
	v_med3_f32 v181, v181, s47, v225
	v_pk_mul_f32 v[228:229], v[180:181], v[180:181]
	v_mov_b32_dpp v183, v179 row_shr:2 row_mask:0xf bank_mask:0xf
	v_pk_fma_f32 v[232:233], v[228:229], s[34:35], v[210:211] op_sel_hi:[1,0,0] neg_lo:[1,0,0] neg_hi:[1,0,0]
	v_lshlrev_b32_e32 v182, 16, v183
	v_pk_fma_f32 v[232:233], v[228:229], v[232:233], s[38:39] op_sel_hi:[1,1,0]
	v_and_b32_e32 v183, 0xffff0000, v183
	v_pk_fma_f32 v[232:233], v[228:229], v[232:233], s[40:41] op_sel_hi:[1,1,0]
; __device__ __forceinline__ unsigned cvt_pk_bf16(float lo, float hi) { unsigned r; asm volatile("v_cvt_pk_bf16_f32 %0, %1, %2" : "=v"(r) : "v"(lo), "v"(hi)); return r; }
;     static __device__ __forceinline__ u32x2 finish2(const float (&g0)[4], const float (&g1)[4], const float (&g2)[4], const float (&w0)[4], const float (&w1)[4], const float (&w2)[4], const float (&bb)[4],
;                                                     const f32x4 v, float rs) {
;         float h[4];
; #pragma unroll
;         for (int j = 0; j < 4; j += 2) {
;             const f32x2 gc = (f32x2){bb[j] + w0[j] * g2[j] + w1[j] * g1[j] + w2[j] * g0[j], bb[j + 1] + w0[j + 1] * g2[j + 1] + w1[j + 1] * g1[j + 1] + w2[j + 1] * g0[j + 1]};
;             const f32x2 ge = gelu_pk(gc) * ((f32x2){v[j], v[j + 1]} * rs); h[j] = ge.x; h[j + 1] = ge.y; }
;         u32x2 w; w.x = cvt_pk_bf16(h[0], h[1]); w.y = cvt_pk_bf16(h[2], h[3]); return w;
;     }
;     __device__ __forceinline__ void operator()(const f32x4 (&acc)[2][2][4][2], const Unit& u, int wr, int wc, int fr, int fq) const {
;     ...
;             for (int ai = 0; ai < 2; ++ai) { const int R0 = u.rb + ai * HALF + wr * 64; const bf16_t* gp = G + (size_t)(R0 + fr) * 2816 + col8;
;                 u32x4 gq[4], prv = (u32x4){0u, 0u, 0u, 0u};
; #pragma unroll
;                 for (int m = 0; m < 4; ++m) gq[m] = *(const u32x4*)(gp + (size_t)m * 16 * 2816);
;                 if ((R0 & 8191) != 0) prv = *(const u32x4*)(gp - (size_t)16 * 2816);
;                 u32x4 pv = prv;
; #pragma unroll
;                 for (int m = 0; m < 4; ++m) { const u32x4 cur = gq[m]; u32x4 hw;
; #pragma unroll
;                     for (int hv = 0; hv < 2; ++hv) { const u32x2 c2 = half2(cur, hv), p2 = half2(pv, hv);
;                         const u32x2 q1 = dpp_prev<1>(p2, c2), q2 = dpp_prev<2>(p2, c2);
;                         float g0[4], g1[4], g2[4]; unpk4(c2, g0); unpk4(q1, g1); unpk4(q2, g2);
;                         const u32x2 r = finish2(g0, g1, g2, w0[hv], w1[hv], w2[hv], bb[hv], acc[ai][bj][m][hv], rs8[ai][m]);
;                         if (hv == 0) { hw.x = r.x; hw.y = r.y; } else { hw.z = r.x; hw.w = r.y; } }
;                     *(u32x4*)(H + (size_t)(R0 + fr + 16 * m) * 2816 + col8) = hw;
;                     pv = cur; } }
	v_pk_mul_f32 v[128:129], v[128:129], 0.5 op_sel_hi:[1,0]
	v_pk_fma_f32 v[232:233], v[228:229], v[232:233], s[42:43] op_sel_hi:[1,1,0]
	v_lshlrev_b32_e32 v130, 16, v131
	v_pk_fma_f32 v[232:233], v[228:229], v[232:233], s[44:45] op_sel_hi:[1,1,0]
	v_and_b32_e32 v131, 0xffff0000, v131
	v_pk_fma_f32 v[232:233], v[228:229], v[232:233], s[46:47] op_sel_hi:[1,1,0]
	v_pk_mul_f32 v[108:109], v[108:109], v[184:185] op_sel_hi:[1,0]
	v_pk_fma_f32 v[228:229], v[228:229], v[232:233], s[48:49] op_sel_hi:[1,1,0]
	v_pk_mul_f32 v[110:111], v[110:111], v[184:185] op_sel_hi:[1,0]
	v_pk_mul_f32 v[180:181], v[180:181], v[228:229]
	v_pk_mul_f32 v[104:105], v[104:105], v[2:3] op_sel_hi:[1,0]
	v_pk_fma_f32 v[128:129], v[128:129], v[180:181], v[128:129]
	v_pk_fma_f32 v[180:181], v[134:135], v[182:183], v[146:147]
	v_pk_mul_f32 v[124:125], v[124:125], v[128:129]
	v_lshlrev_b32_e32 v128, 16, v179
	v_and_b32_e32 v129, 0xffff0000, v179
	v_pk_fma_f32 v[130:131], v[138:139], v[130:131], v[180:181]
	v_cvt_pk_bf16_f32 v228, v124, v125
	v_pk_mul_f32 v[106:107], v[106:107], v[2:3] op_sel_hi:[1,0]
	v_pk_fma_f32 v[128:129], v[142:143], v[128:129], v[130:131]
	v_pk_mul_f32 v[100:101], v[100:101], v[2:3] op_sel_hi:[1,0]
	v_pk_mul_f32 v[130:131], v[128:129], s[30:31] op_sel_hi:[1,0]
	v_pk_mul_f32 v[128:129], v[128:129], 0.5 op_sel_hi:[1,0]
	v_med3_f32 v130, v130, s47, v225
	v_med3_f32 v131, v131, s47, v225
	v_pk_mul_f32 v[180:181], v[130:131], v[130:131]
	s_add_i32 s7, s2, 0x80
	v_pk_fma_f32 v[182:183], v[180:181], s[34:35], v[210:211] op_sel_hi:[1,0,0] neg_lo:[1,0,0] neg_hi:[1,0,0]
	v_readlane_b32 s2, v240, 12
	v_pk_fma_f32 v[182:183], v[180:181], v[182:183], s[38:39] op_sel_hi:[1,1,0]
	v_readlane_b32 s3, v240, 13
	v_pk_fma_f32 v[182:183], v[180:181], v[182:183], s[40:41] op_sel_hi:[1,1,0]
	v_add_u32_e32 v1, s7, v1
	v_pk_fma_f32 v[182:183], v[180:181], v[182:183], s[42:43] op_sel_hi:[1,1,0]
	v_pk_mul_f32 v[102:103], v[102:103], v[2:3] op_sel_hi:[1,0]
	v_pk_fma_f32 v[182:183], v[180:181], v[182:183], s[44:45] op_sel_hi:[1,1,0]
	s_and_b32 s7, s7, 0x1fff
	v_pk_fma_f32 v[182:183], v[180:181], v[182:183], s[46:47] op_sel_hi:[1,1,0]
	s_cmp_lg_u32 s7, 0
	v_pk_fma_f32 v[180:181], v[180:181], v[182:183], s[48:49] op_sel_hi:[1,1,0]
	v_lshlrev_b32_e32 v182, 16, v172
	v_pk_mul_f32 v[130:131], v[130:131], v[180:181]
	v_lshlrev_b64 v[180:181], 1, v[212:213]
	v_pk_fma_f32 v[128:129], v[128:129], v[130:131], v[128:129]
	v_lshl_add_u64 v[130:131], s[8:9], 0, v[230:231]
	v_pk_mul_f32 v[126:127], v[126:127], v[128:129]
	v_lshl_add_u64 v[124:125], v[130:131], 0, v[180:181]
	v_mov_b32_dpp v129, v176 row_ror:2 row_mask:0xf bank_mask:0xf bound_ctrl:1
	v_cvt_pk_bf16_f32 v229, v126, v127
	global_store_dwordx4 v[124:125], v[226:229], off sc1
	v_mov_b32_dpp v125, v176 row_ror:1 row_mask:0xf bank_mask:0xf bound_ctrl:1
	v_mov_b32_dpp v129, v172 row_shr:2 row_mask:0xf bank_mask:0xf
	v_lshlrev_b32_e32 v128, 16, v129
	v_mov_b32_dpp v125, v172 row_shr:1 row_mask:0xf bank_mask:0xf
	v_and_b32_e32 v129, 0xffff0000, v129
	v_lshlrev_b32_e32 v124, 16, v125
	v_and_b32_e32 v125, 0xffff0000, v125
	v_pk_fma_f32 v[128:129], v[148:149], v[128:129], v[160:161]
	v_and_b32_e32 v183, 0xffff0000, v172
	v_pk_fma_f32 v[124:125], v[152:153], v[124:125], v[128:129]
	v_mov_b32_dpp v127, v177 row_ror:1 row_mask:0xf bank_mask:0xf bound_ctrl:1
	v_pk_fma_f32 v[124:125], v[156:157], v[182:183], v[124:125]
	v_mov_b32_dpp v177, v177 row_ror:2 row_mask:0xf bank_mask:0xf bound_ctrl:1
	v_pk_mul_f32 v[128:129], v[124:125], s[30:31] op_sel_hi:[1,0]
	v_mov_b32_dpp v127, v173 row_shr:1 row_mask:0xf bank_mask:0xf
	v_med3_f32 v128, v128, s47, v225
	v_med3_f32 v129, v129, s47, v225
	v_pk_mul_f32 v[182:183], v[128:129], v[128:129]
	v_mov_b32_dpp v177, v173 row_shr:2 row_mask:0xf bank_mask:0xf
	v_pk_fma_f32 v[226:227], v[182:183], s[34:35], v[210:211] op_sel_hi:[1,0,0] neg_lo:[1,0,0] neg_hi:[1,0,0]
	v_lshlrev_b32_e32 v176, 16, v177
	v_pk_fma_f32 v[226:227], v[182:183], v[226:227], s[38:39] op_sel_hi:[1,1,0]
	v_and_b32_e32 v177, 0xffff0000, v177
	v_pk_fma_f32 v[226:227], v[182:183], v[226:227], s[40:41] op_sel_hi:[1,1,0]
	v_pk_mul_f32 v[124:125], v[124:125], 0.5 op_sel_hi:[1,0]
	v_pk_fma_f32 v[226:227], v[182:183], v[226:227], s[42:43] op_sel_hi:[1,1,0]
	v_lshlrev_b32_e32 v126, 16, v127
	v_pk_fma_f32 v[226:227], v[182:183], v[226:227], s[44:45] op_sel_hi:[1,1,0]
	v_and_b32_e32 v127, 0xffff0000, v127
	v_pk_fma_f32 v[226:227], v[182:183], v[226:227], s[46:47] op_sel_hi:[1,1,0]
	s_nop 0
	v_pk_fma_f32 v[182:183], v[182:183], v[226:227], s[48:49] op_sel_hi:[1,1,0]
	s_nop 0
	v_pk_mul_f32 v[128:129], v[128:129], v[182:183]
	s_nop 0
	v_pk_fma_f32 v[124:125], v[124:125], v[128:129], v[124:125]
	v_pk_fma_f32 v[128:129], v[150:151], v[176:177], v[162:163]
	v_pk_mul_f32 v[120:121], v[120:121], v[124:125]
	v_lshlrev_b32_e32 v124, 16, v173
	v_and_b32_e32 v125, 0xffff0000, v173
	v_pk_fma_f32 v[126:127], v[154:155], v[126:127], v[128:129]
	v_cvt_pk_bf16_f32 v120, v120, v121
	s_nop 0
	v_pk_fma_f32 v[124:125], v[158:159], v[124:125], v[126:127]
	s_nop 0
	v_pk_mul_f32 v[126:127], v[124:125], s[30:31] op_sel_hi:[1,0]
	v_pk_mul_f32 v[124:125], v[124:125], 0.5 op_sel_hi:[1,0]
	v_med3_f32 v126, v126, s47, v225
	v_med3_f32 v127, v127, s47, v225
	v_pk_mul_f32 v[128:129], v[126:127], v[126:127]
	s_nop 0
	v_pk_fma_f32 v[176:177], v[128:129], s[34:35], v[210:211] op_sel_hi:[1,0,0] neg_lo:[1,0,0] neg_hi:[1,0,0]
	s_nop 0
	v_pk_fma_f32 v[176:177], v[128:129], v[176:177], s[38:39] op_sel_hi:[1,1,0]
	s_nop 0
	v_pk_fma_f32 v[176:177], v[128:129], v[176:177], s[40:41] op_sel_hi:[1,1,0]
	s_nop 0
	v_pk_fma_f32 v[176:177], v[128:129], v[176:177], s[42:43] op_sel_hi:[1,1,0]
	s_nop 0
; __device__ __forceinline__ unsigned cvt_pk_bf16(float lo, float hi) { unsigned r; asm volatile("v_cvt_pk_bf16_f32 %0, %1, %2" : "=v"(r) : "v"(lo), "v"(hi)); return r; }
;     static __device__ __forceinline__ u32x2 finish2(const float (&g0)[4], const float (&g1)[4], const float (&g2)[4], const float (&w0)[4], const float (&w1)[4], const float (&w2)[4], const float (&bb)[4],
;                                                     const f32x4 v, float rs) {
;         float h[4];
; #pragma unroll
;         for (int j = 0; j < 4; j += 2) {
;             const f32x2 gc = (f32x2){bb[j] + w0[j] * g2[j] + w1[j] * g1[j] + w2[j] * g0[j], bb[j + 1] + w0[j + 1] * g2[j + 1] + w1[j + 1] * g1[j + 1] + w2[j + 1] * g0[j + 1]};
;             const f32x2 ge = gelu_pk(gc) * ((f32x2){v[j], v[j + 1]} * rs); h[j] = ge.x; h[j + 1] = ge.y; }
;         u32x2 w; w.x = cvt_pk_bf16(h[0], h[1]); w.y = cvt_pk_bf16(h[2], h[3]); return w;
;     }
;     __device__ __forceinline__ void operator()(const f32x4 (&acc)[2][2][4][2], const Unit& u, int wr, int wc, int fr, int fq) const {
;     ...
;             for (int ai = 0; ai < 2; ++ai) { const int R0 = u.rb + ai * HALF + wr * 64; const bf16_t* gp = G + (size_t)(R0 + fr) * 2816 + col8;
;                 u32x4 gq[4], prv = (u32x4){0u, 0u, 0u, 0u};
; #pragma unroll
;                 for (int m = 0; m < 4; ++m) gq[m] = *(const u32x4*)(gp + (size_t)m * 16 * 2816);
;                 if ((R0 & 8191) != 0) prv = *(const u32x4*)(gp - (size_t)16 * 2816);
;                 u32x4 pv = prv;
; #pragma unroll
;                 for (int m = 0; m < 4; ++m) { const u32x4 cur = gq[m]; u32x4 hw;
; #pragma unroll
;                     for (int hv = 0; hv < 2; ++hv) { const u32x2 c2 = half2(cur, hv), p2 = half2(pv, hv);
;                         const u32x2 q1 = dpp_prev<1>(p2, c2), q2 = dpp_prev<2>(p2, c2);
;                         float g0[4], g1[4], g2[4]; unpk4(c2, g0); unpk4(q1, g1); unpk4(q2, g2);
;                         const u32x2 r = finish2(g0, g1, g2, w0[hv], w1[hv], w2[hv], bb[hv], acc[ai][bj][m][hv], rs8[ai][m]);
;                         if (hv == 0) { hw.x = r.x; hw.y = r.y; } else { hw.z = r.x; hw.w = r.y; } }
;                     *(u32x4*)(H + (size_t)(R0 + fr + 16 * m) * 2816 + col8) = hw;
;                     pv = cur; } }
	v_pk_fma_f32 v[176:177], v[128:129], v[176:177], s[44:45] op_sel_hi:[1,1,0]
	s_nop 0
	v_pk_fma_f32 v[176:177], v[128:129], v[176:177], s[46:47] op_sel_hi:[1,1,0]
	s_nop 0
	v_pk_fma_f32 v[128:129], v[128:129], v[176:177], s[48:49] op_sel_hi:[1,1,0]
	v_lshlrev_b32_e32 v176, 16, v174
	v_pk_mul_f32 v[126:127], v[126:127], v[128:129]
	v_and_b32_e32 v177, 0xffff0000, v174
	v_pk_fma_f32 v[124:125], v[124:125], v[126:127], v[124:125]
	v_mov_b32_dpp v127, v178 row_ror:2 row_mask:0xf bank_mask:0xf bound_ctrl:1
	v_pk_mul_f32 v[122:123], v[122:123], v[124:125]
	v_mov_b32_dpp v125, v179 row_ror:1 row_mask:0xf bank_mask:0xf bound_ctrl:1
	v_cvt_pk_bf16_f32 v121, v122, v123
	v_mov_b32_dpp v127, v174 row_shr:2 row_mask:0xf bank_mask:0xf
	v_mov_b32_dpp v123, v178 row_ror:1 row_mask:0xf bank_mask:0xf bound_ctrl:1
	v_lshlrev_b32_e32 v126, 16, v127
	v_and_b32_e32 v127, 0xffff0000, v127
	v_mov_b32_dpp v123, v174 row_shr:1 row_mask:0xf bank_mask:0xf
	v_lshlrev_b32_e32 v122, 16, v123
	v_and_b32_e32 v123, 0xffff0000, v123
	v_pk_fma_f32 v[126:127], v[132:133], v[126:127], v[144:145]
	v_mov_b32_dpp v129, v179 row_ror:2 row_mask:0xf bank_mask:0xf bound_ctrl:1
	v_pk_fma_f32 v[122:123], v[136:137], v[122:123], v[126:127]
	v_mov_b32_dpp v125, v175 row_shr:1 row_mask:0xf bank_mask:0xf
	v_pk_fma_f32 v[122:123], v[140:141], v[176:177], v[122:123]
	v_mov_b32_dpp v129, v175 row_shr:2 row_mask:0xf bank_mask:0xf
	v_pk_mul_f32 v[126:127], v[122:123], s[30:31] op_sel_hi:[1,0]
	v_lshlrev_b32_e32 v128, 16, v129
	v_med3_f32 v126, v126, s47, v225
	v_med3_f32 v127, v127, s47, v225
	v_pk_mul_f32 v[176:177], v[126:127], v[126:127]
	v_and_b32_e32 v129, 0xffff0000, v129
	v_pk_fma_f32 v[178:179], v[176:177], s[34:35], v[210:211] op_sel_hi:[1,0,0] neg_lo:[1,0,0] neg_hi:[1,0,0]
	v_pk_mul_f32 v[122:123], v[122:123], 0.5 op_sel_hi:[1,0]
	v_pk_fma_f32 v[178:179], v[176:177], v[178:179], s[38:39] op_sel_hi:[1,1,0]
	v_lshlrev_b32_e32 v124, 16, v125
	v_pk_fma_f32 v[178:179], v[176:177], v[178:179], s[40:41] op_sel_hi:[1,1,0]
	v_and_b32_e32 v125, 0xffff0000, v125
	v_pk_fma_f32 v[178:179], v[176:177], v[178:179], s[42:43] op_sel_hi:[1,1,0]
	s_nop 0
	v_pk_fma_f32 v[178:179], v[176:177], v[178:179], s[44:45] op_sel_hi:[1,1,0]
	s_nop 0
	v_pk_fma_f32 v[178:179], v[176:177], v[178:179], s[46:47] op_sel_hi:[1,1,0]
	s_nop 0
	v_pk_fma_f32 v[176:177], v[176:177], v[178:179], s[48:49] op_sel_hi:[1,1,0]
	s_nop 0
	v_pk_mul_f32 v[126:127], v[126:127], v[176:177]
	s_nop 0
	v_pk_fma_f32 v[122:123], v[122:123], v[126:127], v[122:123]
	v_pk_fma_f32 v[126:127], v[134:135], v[128:129], v[146:147]
	v_pk_mul_f32 v[116:117], v[116:117], v[122:123]
	v_lshlrev_b32_e32 v122, 16, v175
	v_and_b32_e32 v123, 0xffff0000, v175
	v_pk_fma_f32 v[124:125], v[138:139], v[124:125], v[126:127]
	s_nop 0
	v_pk_fma_f32 v[122:123], v[142:143], v[122:123], v[124:125]
	s_nop 0
	v_pk_mul_f32 v[124:125], v[122:123], s[30:31] op_sel_hi:[1,0]
	v_pk_mul_f32 v[122:123], v[122:123], 0.5 op_sel_hi:[1,0]
	v_med3_f32 v124, v124, s47, v225
	v_med3_f32 v125, v125, s47, v225
	v_pk_mul_f32 v[126:127], v[124:125], v[124:125]
	s_nop 0
	v_pk_fma_f32 v[128:129], v[126:127], s[34:35], v[210:211] op_sel_hi:[1,0,0] neg_lo:[1,0,0] neg_hi:[1,0,0]
	s_nop 0
	v_pk_fma_f32 v[128:129], v[126:127], v[128:129], s[38:39] op_sel_hi:[1,1,0]
	s_nop 0
	v_pk_fma_f32 v[128:129], v[126:127], v[128:129], s[40:41] op_sel_hi:[1,1,0]
	s_nop 0
	v_pk_fma_f32 v[128:129], v[126:127], v[128:129], s[42:43] op_sel_hi:[1,1,0]
	s_nop 0
	v_pk_fma_f32 v[128:129], v[126:127], v[128:129], s[44:45] op_sel_hi:[1,1,0]
	s_nop 0
	v_pk_fma_f32 v[128:129], v[126:127], v[128:129], s[46:47] op_sel_hi:[1,1,0]
	s_nop 0
	v_pk_fma_f32 v[126:127], v[126:127], v[128:129], s[48:49] op_sel_hi:[1,1,0]
	s_nop 0
	v_pk_mul_f32 v[124:125], v[124:125], v[126:127]
	v_lshlrev_b32_e32 v126, 16, v168
	v_pk_fma_f32 v[122:123], v[122:123], v[124:125], v[122:123]
	v_and_b32_e32 v127, 0xffff0000, v168
	v_pk_mul_f32 v[118:119], v[118:119], v[122:123]
	v_cvt_pk_bf16_f32 v122, v116, v117
	v_mov_b64_e32 v[116:117], s[8:9]
	v_mad_i64_i32 v[176:177], s[8:9], v194, s91, v[116:117]
	v_cvt_pk_bf16_f32 v123, v118, v119
	v_lshl_add_u64 v[118:119], v[176:177], 0, v[180:181]
	global_store_dwordx4 v[118:119], v[120:123], off sc1
	v_mov_b32_dpp v125, v173 row_ror:2 row_mask:0xf bank_mask:0xf bound_ctrl:1
	v_mov_b32_dpp v119, v172 row_ror:1 row_mask:0xf bank_mask:0xf bound_ctrl:1
	v_mov_b32_dpp v123, v172 row_ror:2 row_mask:0xf bank_mask:0xf bound_ctrl:1
	v_mov_b32_dpp v121, v173 row_ror:1 row_mask:0xf bank_mask:0xf bound_ctrl:1
	v_mov_b32_dpp v119, v168 row_shr:1 row_mask:0xf bank_mask:0xf
	v_mov_b32_dpp v123, v168 row_shr:2 row_mask:0xf bank_mask:0xf
	v_lshlrev_b32_e32 v122, 16, v123
	v_and_b32_e32 v123, 0xffff0000, v123
	v_lshlrev_b32_e32 v118, 16, v119
	v_and_b32_e32 v119, 0xffff0000, v119
	v_pk_fma_f32 v[122:123], v[148:149], v[122:123], v[160:161]
	v_mov_b32_dpp v125, v169 row_shr:2 row_mask:0xf bank_mask:0xf
	v_pk_fma_f32 v[118:119], v[152:153], v[118:119], v[122:123]
	v_mov_b32_dpp v121, v169 row_shr:1 row_mask:0xf bank_mask:0xf
	v_pk_fma_f32 v[118:119], v[156:157], v[126:127], v[118:119]
	v_lshlrev_b32_e32 v124, 16, v125
	v_pk_mul_f32 v[122:123], v[118:119], s[30:31] op_sel_hi:[1,0]
	v_and_b32_e32 v125, 0xffff0000, v125
	v_med3_f32 v122, v122, s47, v225
	v_med3_f32 v123, v123, s47, v225
	v_pk_mul_f32 v[126:127], v[122:123], v[122:123]
	v_pk_mul_f32 v[118:119], v[118:119], 0.5 op_sel_hi:[1,0]
	v_pk_fma_f32 v[128:129], v[126:127], s[34:35], v[210:211] op_sel_hi:[1,0,0] neg_lo:[1,0,0] neg_hi:[1,0,0]
	v_lshlrev_b32_e32 v120, 16, v121
	v_pk_fma_f32 v[128:129], v[126:127], v[128:129], s[38:39] op_sel_hi:[1,1,0]
	v_and_b32_e32 v121, 0xffff0000, v121
; __device__ __forceinline__ unsigned cvt_pk_bf16(float lo, float hi) { unsigned r; asm volatile("v_cvt_pk_bf16_f32 %0, %1, %2" : "=v"(r) : "v"(lo), "v"(hi)); return r; }
;     static __device__ __forceinline__ u32x2 finish2(const float (&g0)[4], const float (&g1)[4], const float (&g2)[4], const float (&w0)[4], const float (&w1)[4], const float (&w2)[4], const float (&bb)[4],
;                                                     const f32x4 v, float rs) {
;         float h[4];
; #pragma unroll
;         for (int j = 0; j < 4; j += 2) {
;             const f32x2 gc = (f32x2){bb[j] + w0[j] * g2[j] + w1[j] * g1[j] + w2[j] * g0[j], bb[j + 1] + w0[j + 1] * g2[j + 1] + w1[j + 1] * g1[j + 1] + w2[j + 1] * g0[j + 1]};
;             const f32x2 ge = gelu_pk(gc) * ((f32x2){v[j], v[j + 1]} * rs); h[j] = ge.x; h[j + 1] = ge.y; }
;         u32x2 w; w.x = cvt_pk_bf16(h[0], h[1]); w.y = cvt_pk_bf16(h[2], h[3]); return w;
;     }
;     __device__ __forceinline__ void operator()(const f32x4 (&acc)[2][2][4][2], const Unit& u, int wr, int wc, int fr, int fq) const {
;     ...
;             for (int ai = 0; ai < 2; ++ai) { const int R0 = u.rb + ai * HALF + wr * 64; const bf16_t* gp = G + (size_t)(R0 + fr) * 2816 + col8;
;                 u32x4 gq[4], prv = (u32x4){0u, 0u, 0u, 0u};
; #pragma unroll
;                 for (int m = 0; m < 4; ++m) gq[m] = *(const u32x4*)(gp + (size_t)m * 16 * 2816);
;                 if ((R0 & 8191) != 0) prv = *(const u32x4*)(gp - (size_t)16 * 2816);
;                 u32x4 pv = prv;
; #pragma unroll
;                 for (int m = 0; m < 4; ++m) { const u32x4 cur = gq[m]; u32x4 hw;
; #pragma unroll
;                     for (int hv = 0; hv < 2; ++hv) { const u32x2 c2 = half2(cur, hv), p2 = half2(pv, hv);
;                         const u32x2 q1 = dpp_prev<1>(p2, c2), q2 = dpp_prev<2>(p2, c2);
;                         float g0[4], g1[4], g2[4]; unpk4(c2, g0); unpk4(q1, g1); unpk4(q2, g2);
;                         const u32x2 r = finish2(g0, g1, g2, w0[hv], w1[hv], w2[hv], bb[hv], acc[ai][bj][m][hv], rs8[ai][m]);
;                         if (hv == 0) { hw.x = r.x; hw.y = r.y; } else { hw.z = r.x; hw.w = r.y; } }
;                     *(u32x4*)(H + (size_t)(R0 + fr + 16 * m) * 2816 + col8) = hw;
;                     pv = cur; } }
	v_pk_fma_f32 v[128:129], v[126:127], v[128:129], s[40:41] op_sel_hi:[1,1,0]
	v_mad_i64_i32 v[172:173], s[8:9], v192, s91, v[116:117]
	v_pk_fma_f32 v[128:129], v[126:127], v[128:129], s[42:43] op_sel_hi:[1,1,0]
	s_nop 0
	v_pk_fma_f32 v[128:129], v[126:127], v[128:129], s[44:45] op_sel_hi:[1,1,0]
	s_nop 0
	v_pk_fma_f32 v[128:129], v[126:127], v[128:129], s[46:47] op_sel_hi:[1,1,0]
	s_nop 0
	v_pk_fma_f32 v[126:127], v[126:127], v[128:129], s[48:49] op_sel_hi:[1,1,0]
	s_nop 0
	v_pk_mul_f32 v[122:123], v[122:123], v[126:127]
	s_nop 0
	v_pk_fma_f32 v[118:119], v[118:119], v[122:123], v[118:119]
	v_pk_fma_f32 v[122:123], v[150:151], v[124:125], v[162:163]
	v_pk_mul_f32 v[112:113], v[112:113], v[118:119]
	v_lshlrev_b32_e32 v118, 16, v169
	v_and_b32_e32 v119, 0xffff0000, v169
	v_pk_fma_f32 v[120:121], v[154:155], v[120:121], v[122:123]
	v_cvt_pk_bf16_f32 v112, v112, v113
	s_nop 0
	v_pk_fma_f32 v[118:119], v[158:159], v[118:119], v[120:121]
	s_nop 0
	v_pk_mul_f32 v[120:121], v[118:119], s[30:31] op_sel_hi:[1,0]
	v_pk_mul_f32 v[118:119], v[118:119], 0.5 op_sel_hi:[1,0]
	v_med3_f32 v120, v120, s47, v225
	v_med3_f32 v121, v121, s47, v225
	v_pk_mul_f32 v[122:123], v[120:121], v[120:121]
	s_nop 0
	v_pk_fma_f32 v[124:125], v[122:123], s[34:35], v[210:211] op_sel_hi:[1,0,0] neg_lo:[1,0,0] neg_hi:[1,0,0]
	s_nop 0
	v_pk_fma_f32 v[124:125], v[122:123], v[124:125], s[38:39] op_sel_hi:[1,1,0]
	s_nop 0
	v_pk_fma_f32 v[124:125], v[122:123], v[124:125], s[40:41] op_sel_hi:[1,1,0]
	s_nop 0
	v_pk_fma_f32 v[124:125], v[122:123], v[124:125], s[42:43] op_sel_hi:[1,1,0]
	s_nop 0
	v_pk_fma_f32 v[124:125], v[122:123], v[124:125], s[44:45] op_sel_hi:[1,1,0]
	s_nop 0
	v_pk_fma_f32 v[124:125], v[122:123], v[124:125], s[46:47] op_sel_hi:[1,1,0]
	s_nop 0
	v_pk_fma_f32 v[122:123], v[122:123], v[124:125], s[48:49] op_sel_hi:[1,1,0]
	v_lshlrev_b32_e32 v124, 16, v170
	v_pk_mul_f32 v[120:121], v[120:121], v[122:123]
	v_and_b32_e32 v125, 0xffff0000, v170
	v_pk_fma_f32 v[118:119], v[118:119], v[120:121], v[118:119]
	v_mov_b32_dpp v121, v174 row_ror:2 row_mask:0xf bank_mask:0xf bound_ctrl:1
	v_pk_mul_f32 v[114:115], v[114:115], v[118:119]
	v_mov_b32_dpp v123, v175 row_ror:2 row_mask:0xf bank_mask:0xf bound_ctrl:1
	v_cvt_pk_bf16_f32 v113, v114, v115
	v_mov_b32_dpp v121, v170 row_shr:2 row_mask:0xf bank_mask:0xf
	v_mov_b32_dpp v115, v174 row_ror:1 row_mask:0xf bank_mask:0xf bound_ctrl:1
	v_lshlrev_b32_e32 v120, 16, v121
	v_and_b32_e32 v121, 0xffff0000, v121
	v_mov_b32_dpp v115, v170 row_shr:1 row_mask:0xf bank_mask:0xf
	v_lshlrev_b32_e32 v114, 16, v115
	v_and_b32_e32 v115, 0xffff0000, v115
	v_pk_fma_f32 v[120:121], v[132:133], v[120:121], v[144:145]
	v_mov_b32_dpp v119, v175 row_ror:1 row_mask:0xf bank_mask:0xf bound_ctrl:1
	v_pk_fma_f32 v[114:115], v[136:137], v[114:115], v[120:121]
	v_mov_b32_dpp v123, v171 row_shr:2 row_mask:0xf bank_mask:0xf
	v_pk_fma_f32 v[114:115], v[140:141], v[124:125], v[114:115]
	v_mov_b32_dpp v119, v171 row_shr:1 row_mask:0xf bank_mask:0xf
	v_pk_mul_f32 v[120:121], v[114:115], s[30:31] op_sel_hi:[1,0]
	v_lshlrev_b32_e32 v122, 16, v123
	v_med3_f32 v120, v120, s47, v225
	v_med3_f32 v121, v121, s47, v225
	v_pk_mul_f32 v[124:125], v[120:121], v[120:121]
	v_and_b32_e32 v123, 0xffff0000, v123
	v_pk_fma_f32 v[126:127], v[124:125], s[34:35], v[210:211] op_sel_hi:[1,0,0] neg_lo:[1,0,0] neg_hi:[1,0,0]
	v_pk_mul_f32 v[114:115], v[114:115], 0.5 op_sel_hi:[1,0]
	v_pk_fma_f32 v[126:127], v[124:125], v[126:127], s[38:39] op_sel_hi:[1,1,0]
	v_lshlrev_b32_e32 v118, 16, v119
	v_pk_fma_f32 v[126:127], v[124:125], v[126:127], s[40:41] op_sel_hi:[1,1,0]
	v_and_b32_e32 v119, 0xffff0000, v119
	v_pk_fma_f32 v[126:127], v[124:125], v[126:127], s[42:43] op_sel_hi:[1,1,0]
	s_nop 0
	v_pk_fma_f32 v[126:127], v[124:125], v[126:127], s[44:45] op_sel_hi:[1,1,0]
	s_nop 0
	v_pk_fma_f32 v[126:127], v[124:125], v[126:127], s[46:47] op_sel_hi:[1,1,0]
	s_nop 0
	v_pk_fma_f32 v[124:125], v[124:125], v[126:127], s[48:49] op_sel_hi:[1,1,0]
	s_nop 0
	v_pk_mul_f32 v[120:121], v[120:121], v[124:125]
	s_nop 0
	v_pk_fma_f32 v[114:115], v[114:115], v[120:121], v[114:115]
	v_pk_fma_f32 v[120:121], v[134:135], v[122:123], v[146:147]
	v_pk_mul_f32 v[108:109], v[108:109], v[114:115]
	v_lshlrev_b32_e32 v114, 16, v171
	v_and_b32_e32 v115, 0xffff0000, v171
	v_pk_fma_f32 v[118:119], v[138:139], v[118:119], v[120:121]
	s_nop 0
	v_pk_fma_f32 v[114:115], v[142:143], v[114:115], v[118:119]
	s_nop 0
	v_pk_mul_f32 v[118:119], v[114:115], s[30:31] op_sel_hi:[1,0]
	v_pk_mul_f32 v[114:115], v[114:115], 0.5 op_sel_hi:[1,0]
	v_med3_f32 v118, v118, s47, v225
	v_med3_f32 v119, v119, s47, v225
	v_pk_mul_f32 v[120:121], v[118:119], v[118:119]
	s_nop 0
	v_pk_fma_f32 v[122:123], v[120:121], s[34:35], v[210:211] op_sel_hi:[1,0,0] neg_lo:[1,0,0] neg_hi:[1,0,0]
	s_nop 0
	v_pk_fma_f32 v[122:123], v[120:121], v[122:123], s[38:39] op_sel_hi:[1,1,0]
	s_nop 0
	v_pk_fma_f32 v[122:123], v[120:121], v[122:123], s[40:41] op_sel_hi:[1,1,0]
	s_nop 0
	v_pk_fma_f32 v[122:123], v[120:121], v[122:123], s[42:43] op_sel_hi:[1,1,0]
	s_nop 0
	v_pk_fma_f32 v[122:123], v[120:121], v[122:123], s[44:45] op_sel_hi:[1,1,0]
	s_nop 0
	v_pk_fma_f32 v[122:123], v[120:121], v[122:123], s[46:47] op_sel_hi:[1,1,0]
	s_nop 0
	v_pk_fma_f32 v[120:121], v[120:121], v[122:123], s[48:49] op_sel_hi:[1,1,0]
	s_nop 0
	v_pk_mul_f32 v[118:119], v[118:119], v[120:121]
	s_nop 0
	v_pk_fma_f32 v[114:115], v[114:115], v[118:119], v[114:115]
	v_lshlrev_b32_e32 v118, 16, v164
	v_pk_mul_f32 v[110:111], v[110:111], v[114:115]
	v_cvt_pk_bf16_f32 v114, v108, v109
	v_lshl_add_u64 v[108:109], v[172:173], 0, v[180:181]
	v_cvt_pk_bf16_f32 v115, v110, v111
	global_store_dwordx4 v[108:109], v[112:115], off sc1
; __device__ __forceinline__ unsigned cvt_pk_bf16(float lo, float hi) { unsigned r; asm volatile("v_cvt_pk_bf16_f32 %0, %1, %2" : "=v"(r) : "v"(lo), "v"(hi)); return r; }
;     static __device__ __forceinline__ u32x2 finish2(const float (&g0)[4], const float (&g1)[4], const float (&g2)[4], const float (&w0)[4], const float (&w1)[4], const float (&w2)[4], const float (&bb)[4],
;                                                     const f32x4 v, float rs) {
;         float h[4];
; #pragma unroll
;         for (int j = 0; j < 4; j += 2) {
;             const f32x2 gc = (f32x2){bb[j] + w0[j] * g2[j] + w1[j] * g1[j] + w2[j] * g0[j], bb[j + 1] + w0[j + 1] * g2[j + 1] + w1[j + 1] * g1[j + 1] + w2[j + 1] * g0[j + 1]};
;             const f32x2 ge = gelu_pk(gc) * ((f32x2){v[j], v[j + 1]} * rs); h[j] = ge.x; h[j + 1] = ge.y; }
;         u32x2 w; w.x = cvt_pk_bf16(h[0], h[1]); w.y = cvt_pk_bf16(h[2], h[3]); return w;
;     }
;     __device__ __forceinline__ void operator()(const f32x4 (&acc)[2][2][4][2], const Unit& u, int wr, int wc, int fr, int fq) const {
;     ...
;             for (int ai = 0; ai < 2; ++ai) { const int R0 = u.rb + ai * HALF + wr * 64; const bf16_t* gp = G + (size_t)(R0 + fr) * 2816 + col8;
;                 u32x4 gq[4], prv = (u32x4){0u, 0u, 0u, 0u};
; #pragma unroll
;                 for (int m = 0; m < 4; ++m) gq[m] = *(const u32x4*)(gp + (size_t)m * 16 * 2816);
;                 if ((R0 & 8191) != 0) prv = *(const u32x4*)(gp - (size_t)16 * 2816);
;                 u32x4 pv = prv;
; #pragma unroll
;                 for (int m = 0; m < 4; ++m) { const u32x4 cur = gq[m]; u32x4 hw;
; #pragma unroll
;                     for (int hv = 0; hv < 2; ++hv) { const u32x2 c2 = half2(cur, hv), p2 = half2(pv, hv);
;                         const u32x2 q1 = dpp_prev<1>(p2, c2), q2 = dpp_prev<2>(p2, c2);
;                         float g0[4], g1[4], g2[4]; unpk4(c2, g0); unpk4(q1, g1); unpk4(q2, g2);
;                         const u32x2 r = finish2(g0, g1, g2, w0[hv], w1[hv], w2[hv], bb[hv], acc[ai][bj][m][hv], rs8[ai][m]);
;                         if (hv == 0) { hw.x = r.x; hw.y = r.y; } else { hw.z = r.x; hw.w = r.y; } }
;                     *(u32x4*)(H + (size_t)(R0 + fr + 16 * m) * 2816 + col8) = hw;
;                     pv = cur; } }
	v_and_b32_e32 v119, 0xffff0000, v164
	v_mov_b32_dpp v109, v168 row_ror:1 row_mask:0xf bank_mask:0xf bound_ctrl:1
	v_mov_b32_dpp v113, v168 row_ror:2 row_mask:0xf bank_mask:0xf bound_ctrl:1
	v_mov_b32_dpp v115, v169 row_ror:2 row_mask:0xf bank_mask:0xf bound_ctrl:1
	v_mov_b32_dpp v109, v164 row_shr:1 row_mask:0xf bank_mask:0xf
	v_mov_b32_dpp v113, v164 row_shr:2 row_mask:0xf bank_mask:0xf
	v_lshlrev_b32_e32 v112, 16, v113
	v_and_b32_e32 v113, 0xffff0000, v113
	v_lshlrev_b32_e32 v108, 16, v109
	v_and_b32_e32 v109, 0xffff0000, v109
	v_pk_fma_f32 v[112:113], v[148:149], v[112:113], v[160:161]
	v_mov_b32_dpp v111, v169 row_ror:1 row_mask:0xf bank_mask:0xf bound_ctrl:1
	v_pk_fma_f32 v[108:109], v[152:153], v[108:109], v[112:113]
	v_mov_b32_dpp v115, v165 row_shr:2 row_mask:0xf bank_mask:0xf
	v_pk_fma_f32 v[108:109], v[156:157], v[118:119], v[108:109]
	v_mov_b32_dpp v111, v165 row_shr:1 row_mask:0xf bank_mask:0xf
	v_pk_mul_f32 v[112:113], v[108:109], s[30:31] op_sel_hi:[1,0]
	v_lshlrev_b32_e32 v114, 16, v115
	v_med3_f32 v112, v112, s47, v225
	v_med3_f32 v113, v113, s47, v225
	v_pk_mul_f32 v[118:119], v[112:113], v[112:113]
	v_and_b32_e32 v115, 0xffff0000, v115
	v_pk_fma_f32 v[120:121], v[118:119], s[34:35], v[210:211] op_sel_hi:[1,0,0] neg_lo:[1,0,0] neg_hi:[1,0,0]
	v_pk_mul_f32 v[108:109], v[108:109], 0.5 op_sel_hi:[1,0]
	v_pk_fma_f32 v[120:121], v[118:119], v[120:121], s[38:39] op_sel_hi:[1,1,0]
	v_lshlrev_b32_e32 v110, 16, v111
	v_pk_fma_f32 v[120:121], v[118:119], v[120:121], s[40:41] op_sel_hi:[1,1,0]
	v_and_b32_e32 v111, 0xffff0000, v111
	v_pk_fma_f32 v[120:121], v[118:119], v[120:121], s[42:43] op_sel_hi:[1,1,0]
	s_nop 0
	v_pk_fma_f32 v[120:121], v[118:119], v[120:121], s[44:45] op_sel_hi:[1,1,0]
	s_nop 0
	v_pk_fma_f32 v[120:121], v[118:119], v[120:121], s[46:47] op_sel_hi:[1,1,0]
	s_nop 0
	v_pk_fma_f32 v[118:119], v[118:119], v[120:121], s[48:49] op_sel_hi:[1,1,0]
	s_nop 0
	v_pk_mul_f32 v[112:113], v[112:113], v[118:119]
	s_nop 0
	v_pk_fma_f32 v[108:109], v[108:109], v[112:113], v[108:109]
	v_pk_fma_f32 v[112:113], v[150:151], v[114:115], v[162:163]
	v_pk_mul_f32 v[104:105], v[104:105], v[108:109]
	v_lshlrev_b32_e32 v108, 16, v165
	v_and_b32_e32 v109, 0xffff0000, v165
	v_pk_fma_f32 v[110:111], v[154:155], v[110:111], v[112:113]
	v_cvt_pk_bf16_f32 v120, v104, v105
	v_mov_b32_dpp v105, v170 row_ror:1 row_mask:0xf bank_mask:0xf bound_ctrl:1
	v_pk_fma_f32 v[108:109], v[158:159], v[108:109], v[110:111]
	s_nop 0
	v_pk_mul_f32 v[110:111], v[108:109], s[30:31] op_sel_hi:[1,0]
	v_pk_mul_f32 v[108:109], v[108:109], 0.5 op_sel_hi:[1,0]
	v_med3_f32 v110, v110, s47, v225
	v_med3_f32 v111, v111, s47, v225
	v_pk_mul_f32 v[112:113], v[110:111], v[110:111]
	v_mov_b32_dpp v105, v166 row_shr:1 row_mask:0xf bank_mask:0xf
	v_pk_fma_f32 v[114:115], v[112:113], s[34:35], v[210:211] op_sel_hi:[1,0,0] neg_lo:[1,0,0] neg_hi:[1,0,0]
	v_lshlrev_b32_e32 v104, 16, v105
	v_pk_fma_f32 v[114:115], v[112:113], v[114:115], s[38:39] op_sel_hi:[1,1,0]
	v_and_b32_e32 v105, 0xffff0000, v105
	v_pk_fma_f32 v[114:115], v[112:113], v[114:115], s[40:41] op_sel_hi:[1,1,0]
	s_nop 0
	v_pk_fma_f32 v[114:115], v[112:113], v[114:115], s[42:43] op_sel_hi:[1,1,0]
	s_nop 0
	v_pk_fma_f32 v[114:115], v[112:113], v[114:115], s[44:45] op_sel_hi:[1,1,0]
	s_nop 0
	v_pk_fma_f32 v[114:115], v[112:113], v[114:115], s[46:47] op_sel_hi:[1,1,0]
	s_nop 0
	v_pk_fma_f32 v[112:113], v[112:113], v[114:115], s[48:49] op_sel_hi:[1,1,0]
	s_nop 0
	v_pk_mul_f32 v[110:111], v[110:111], v[112:113]
	v_lshlrev_b32_e32 v112, 16, v166
	v_pk_fma_f32 v[108:109], v[108:109], v[110:111], v[108:109]
	v_and_b32_e32 v113, 0xffff0000, v166
	v_pk_mul_f32 v[106:107], v[106:107], v[108:109]
	v_mov_b32_dpp v109, v170 row_ror:2 row_mask:0xf bank_mask:0xf bound_ctrl:1
	v_mov_b32_dpp v111, v171 row_ror:2 row_mask:0xf bank_mask:0xf bound_ctrl:1
	v_cvt_pk_bf16_f32 v121, v106, v107
	v_mov_b32_dpp v107, v171 row_ror:1 row_mask:0xf bank_mask:0xf bound_ctrl:1
; __device__ __forceinline__ unsigned cvt_pk_bf16(float lo, float hi) { unsigned r; asm volatile("v_cvt_pk_bf16_f32 %0, %1, %2" : "=v"(r) : "v"(lo), "v"(hi)); return r; }
;     static __device__ __forceinline__ u32x2 finish2(const float (&g0)[4], const float (&g1)[4], const float (&g2)[4], const float (&w0)[4], const float (&w1)[4], const float (&w2)[4], const float (&bb)[4],
;                                                     const f32x4 v, float rs) {
;         float h[4];
; #pragma unroll
;         for (int j = 0; j < 4; j += 2) {
;             const f32x2 gc = (f32x2){bb[j] + w0[j] * g2[j] + w1[j] * g1[j] + w2[j] * g0[j], bb[j + 1] + w0[j + 1] * g2[j + 1] + w1[j + 1] * g1[j + 1] + w2[j + 1] * g0[j + 1]};
;             const f32x2 ge = gelu_pk(gc) * ((f32x2){v[j], v[j + 1]} * rs); h[j] = ge.x; h[j + 1] = ge.y; }
;         u32x2 w; w.x = cvt_pk_bf16(h[0], h[1]); w.y = cvt_pk_bf16(h[2], h[3]); return w;
;     }
;     __device__ __forceinline__ void operator()(const f32x4 (&acc)[2][2][4][2], const Unit& u, int wr, int wc, int fr, int fq) const {
;     ...
;             for (int ai = 0; ai < 2; ++ai) { const int R0 = u.rb + ai * HALF + wr * 64; const bf16_t* gp = G + (size_t)(R0 + fr) * 2816 + col8;
;                 u32x4 gq[4], prv = (u32x4){0u, 0u, 0u, 0u};
; #pragma unroll
;                 for (int m = 0; m < 4; ++m) gq[m] = *(const u32x4*)(gp + (size_t)m * 16 * 2816);
;                 if ((R0 & 8191) != 0) prv = *(const u32x4*)(gp - (size_t)16 * 2816);
;                 u32x4 pv = prv;
; #pragma unroll
;                 for (int m = 0; m < 4; ++m) { const u32x4 cur = gq[m]; u32x4 hw;
; #pragma unroll
;                     for (int hv = 0; hv < 2; ++hv) { const u32x2 c2 = half2(cur, hv), p2 = half2(pv, hv);
;                         const u32x2 q1 = dpp_prev<1>(p2, c2), q2 = dpp_prev<2>(p2, c2);
;                         float g0[4], g1[4], g2[4]; unpk4(c2, g0); unpk4(q1, g1); unpk4(q2, g2);
;                         const u32x2 r = finish2(g0, g1, g2, w0[hv], w1[hv], w2[hv], bb[hv], acc[ai][bj][m][hv], rs8[ai][m]);
;                         if (hv == 0) { hw.x = r.x; hw.y = r.y; } else { hw.z = r.x; hw.w = r.y; } }
;                     *(u32x4*)(H + (size_t)(R0 + fr + 16 * m) * 2816 + col8) = hw;
;                     pv = cur; } }
	v_mov_b32_dpp v109, v166 row_shr:2 row_mask:0xf bank_mask:0xf
	v_lshlrev_b32_e32 v108, 16, v109
	v_and_b32_e32 v109, 0xffff0000, v109
	v_pk_fma_f32 v[108:109], v[132:133], v[108:109], v[144:145]
	v_mov_b32_dpp v111, v167 row_shr:2 row_mask:0xf bank_mask:0xf
	v_pk_fma_f32 v[104:105], v[136:137], v[104:105], v[108:109]
	v_mov_b32_dpp v107, v167 row_shr:1 row_mask:0xf bank_mask:0xf
	v_pk_fma_f32 v[104:105], v[140:141], v[112:113], v[104:105]
	v_lshlrev_b32_e32 v110, 16, v111
	v_pk_mul_f32 v[108:109], v[104:105], s[30:31] op_sel_hi:[1,0]
	v_and_b32_e32 v111, 0xffff0000, v111
	v_med3_f32 v108, v108, s47, v225
	v_med3_f32 v109, v109, s47, v225
	v_pk_mul_f32 v[112:113], v[108:109], v[108:109]
	v_pk_mul_f32 v[104:105], v[104:105], 0.5 op_sel_hi:[1,0]
	v_pk_fma_f32 v[114:115], v[112:113], s[34:35], v[210:211] op_sel_hi:[1,0,0] neg_lo:[1,0,0] neg_hi:[1,0,0]
	v_lshlrev_b32_e32 v106, 16, v107
	v_pk_fma_f32 v[114:115], v[112:113], v[114:115], s[38:39] op_sel_hi:[1,1,0]
	v_and_b32_e32 v107, 0xffff0000, v107
	v_pk_fma_f32 v[114:115], v[112:113], v[114:115], s[40:41] op_sel_hi:[1,1,0]
	s_nop 0
	v_pk_fma_f32 v[114:115], v[112:113], v[114:115], s[42:43] op_sel_hi:[1,1,0]
	s_nop 0
	v_pk_fma_f32 v[114:115], v[112:113], v[114:115], s[44:45] op_sel_hi:[1,1,0]
	s_nop 0
	v_pk_fma_f32 v[114:115], v[112:113], v[114:115], s[46:47] op_sel_hi:[1,1,0]
	s_nop 0
	v_pk_fma_f32 v[112:113], v[112:113], v[114:115], s[48:49] op_sel_hi:[1,1,0]
	s_nop 0
	v_pk_mul_f32 v[108:109], v[108:109], v[112:113]
	s_nop 0
	v_pk_fma_f32 v[104:105], v[104:105], v[108:109], v[104:105]
	v_pk_fma_f32 v[108:109], v[134:135], v[110:111], v[146:147]
	v_pk_mul_f32 v[100:101], v[100:101], v[104:105]
	v_lshlrev_b32_e32 v104, 16, v167
	v_and_b32_e32 v105, 0xffff0000, v167
	v_pk_fma_f32 v[106:107], v[138:139], v[106:107], v[108:109]
	v_cvt_pk_bf16_f32 v122, v100, v101
	v_mov_b64_e32 v[100:101], s[2:3]
	v_pk_fma_f32 v[104:105], v[142:143], v[104:105], v[106:107]
	v_mad_i64_i32 v[164:165], s[2:3], v1, s91, v[100:101]
	v_pk_mul_f32 v[106:107], v[104:105], s[30:31] op_sel_hi:[1,0]
	v_lshl_add_u64 v[118:119], v[164:165], 0, v[180:181]
	v_med3_f32 v106, v106, s47, v225
	v_med3_f32 v107, v107, s47, v225
	v_pk_mul_f32 v[108:109], v[106:107], v[106:107]
	v_pk_mul_f32 v[104:105], v[104:105], 0.5 op_sel_hi:[1,0]
	v_pk_fma_f32 v[110:111], v[108:109], s[34:35], v[210:211] op_sel_hi:[1,0,0] neg_lo:[1,0,0] neg_hi:[1,0,0]
	v_add_co_u32_e32 v100, vcc, s10, v118
	v_pk_fma_f32 v[110:111], v[108:109], v[110:111], s[38:39] op_sel_hi:[1,1,0]
	s_nop 0
	v_addc_co_u32_e32 v101, vcc, 0, v119, vcc
	v_pk_fma_f32 v[110:111], v[108:109], v[110:111], s[40:41] op_sel_hi:[1,1,0]
	v_mad_i64_i32 v[166:167], s[2:3], v190, s91, v[116:117]
	v_pk_fma_f32 v[110:111], v[108:109], v[110:111], s[42:43] op_sel_hi:[1,1,0]
	v_lshl_add_u64 v[116:117], v[166:167], 0, v[180:181]
	v_pk_fma_f32 v[110:111], v[108:109], v[110:111], s[44:45] op_sel_hi:[1,1,0]
	s_cselect_b64 s[2:3], -1, 0
	v_pk_fma_f32 v[110:111], v[108:109], v[110:111], s[46:47] op_sel_hi:[1,1,0]
	s_cmp_eq_u32 s7, 0
	v_pk_fma_f32 v[108:109], v[108:109], v[110:111], s[48:49] op_sel_hi:[1,1,0]
	s_nop 0
	v_pk_mul_f32 v[106:107], v[106:107], v[108:109]
	s_nop 0
	v_pk_fma_f32 v[104:105], v[104:105], v[106:107], v[104:105]
	s_nop 0
	v_pk_mul_f32 v[102:103], v[102:103], v[104:105]
	s_nop 0
	v_cvt_pk_bf16_f32 v123, v102, v103
	global_load_dwordx4 v[112:115], v[118:119], off
	global_load_dwordx4 v[108:111], v[100:101], off
	v_add_co_u32_e32 v100, vcc, 0x2c000, v118
	s_nop 1
	v_addc_co_u32_e32 v101, vcc, 0, v119, vcc
	v_add_co_u32_e32 v102, vcc, 0x42000, v118
	s_nop 1
	v_addc_co_u32_e32 v103, vcc, 0, v119, vcc
	global_load_dwordx4 v[104:107], v[100:101], off
	s_nop 0
	global_load_dwordx4 v[100:103], v[102:103], off
	s_nop 0
	global_store_dwordx4 v[116:117], v[120:123], off sc1
	s_cbranch_scc1 .LBB0_1015
	v_add_co_u32_e32 v116, vcc, 0xfffea000, v118
	s_nop 1
	v_addc_co_u32_e32 v117, vcc, -1, v119, vcc
	global_load_dwordx4 v[116:119], v[116:117], off
	s_branch .LBB0_1016

;     static __device__ __forceinline__ u32x2 finish2(const float (&g0)[4], const float (&g1)[4], const float (&g2)[4], const float (&w0)[4], const float (&w1)[4], const float (&w2)[4], const float (&bb)[4],
;                                                     const f32x4 v, float rs) {
;         float h[4];
; #pragma unroll
;         for (int j = 0; j < 4; j += 2) {
;             const f32x2 gc = (f32x2){bb[j] + w0[j] * g2[j] + w1[j] * g1[j] + w2[j] * g0[j], bb[j + 1] + w0[j + 1] * g2[j + 1] + w1[j + 1] * g1[j + 1] + w2[j + 1] * g0[j + 1]};
;             const f32x2 ge = gelu_pk(gc) * ((f32x2){v[j], v[j + 1]} * rs); h[j] = ge.x; h[j + 1] = ge.y; }
;         u32x2 w; w.x = cvt_pk_bf16(h[0], h[1]); w.y = cvt_pk_bf16(h[2], h[3]); return w;
;     }
;     __device__ __forceinline__ void operator()(const f32x4 (&acc)[2][2][4][2], const Unit& u, int wr, int wc, int fr, int fq) const {
;     ...
;             for (int m = 0; m < 4; ++m) rs8[ai][m] = rsqrtf(SS[u.rb + (u.half ? 0 : ai * HALF) + wr * 64 + fr + 16 * m] * (1.f / 1024.f) + 1e-6f);
;     ...
;             for (int ai = 0; ai < 2; ++ai) { const int R0 = u.rb + ai * HALF + wr * 64; const bf16_t* gp = G + (size_t)(R0 + fr) * 2816 + col8;
;                 u32x4 gq[4], prv = (u32x4){0u, 0u, 0u, 0u};
; #pragma unroll
;                 for (int m = 0; m < 4; ++m) gq[m] = *(const u32x4*)(gp + (size_t)m * 16 * 2816);
;                 if ((R0 & 8191) != 0) prv = *(const u32x4*)(gp - (size_t)16 * 2816);
;                 u32x4 pv = prv;
; #pragma unroll
;                 for (int m = 0; m < 4; ++m) { const u32x4 cur = gq[m]; u32x4 hw;
; #pragma unroll
;                     for (int hv = 0; hv < 2; ++hv) { const u32x2 c2 = half2(cur, hv), p2 = half2(pv, hv);
;                         const u32x2 q1 = dpp_prev<1>(p2, c2), q2 = dpp_prev<2>(p2, c2);
;                         float g0[4], g1[4], g2[4]; unpk4(c2, g0); unpk4(q1, g1); unpk4(q2, g2);
;                         const u32x2 r = finish2(g0, g1, g2, w0[hv], w1[hv], w2[hv], bb[hv], acc[ai][bj][m][hv], rs8[ai][m]);
;                         if (hv == 0) { hw.x = r.x; hw.y = r.y; } else { hw.z = r.x; hw.w = r.y; } }
;                     *(u32x4*)(H + (size_t)(R0 + fr + 16 * m) * 2816 + col8) = hw;
;                     pv = cur; } }
.LBB0_1016:
	v_fmamk_f32 v122, v189, 0x3a800000, v224
	v_cmp_gt_f32_e32 vcc, s5, v122
	v_mul_f32_e32 v123, 0x4b800000, v122
	v_fmamk_f32 v3, v3, 0x3a800000, v224
	v_cndmask_b32_e32 v122, v122, v123, vcc
	v_rsq_f32_e32 v122, v122
	s_waitcnt vmcnt(0)
	v_mov_b32_dpp v125, v116 row_ror:2 row_mask:0xf bank_mask:0xf bound_ctrl:1
	v_mov_b32_dpp v127, v117 row_ror:2 row_mask:0xf bank_mask:0xf bound_ctrl:1
	v_lshlrev_b32_e32 v178, 16, v112
	v_mul_f32_e32 v123, 0x45800000, v122
	v_cndmask_b32_e32 v128, v122, v123, vcc
	v_fmamk_f32 v122, v187, 0x3a800000, v224
	v_cmp_gt_f32_e32 vcc, s5, v122
	v_mul_f32_e32 v123, 0x4b800000, v122
	v_mov_b32_dpp v125, v112 row_shr:2 row_mask:0xf bank_mask:0xf
	v_cndmask_b32_e32 v122, v122, v123, vcc
	v_rsq_f32_e32 v122, v122
	v_lshlrev_b32_e32 v170, 16, v125
	v_and_b32_e32 v171, 0xffff0000, v125
	v_pk_fma_f32 v[170:171], v[148:149], v[170:171], v[160:161]
	v_mul_f32_e32 v123, 0x45800000, v122
	v_cndmask_b32_e32 v126, v122, v123, vcc
	v_cmp_gt_f32_e32 vcc, s5, v3
	v_mul_f32_e32 v122, 0x4b800000, v3
	v_mov_b32_dpp v123, v117 row_ror:1 row_mask:0xf bank_mask:0xf bound_ctrl:1
	v_cndmask_b32_e32 v3, v3, v122, vcc
	v_rsq_f32_e32 v3, v3
	v_and_b32_e32 v179, 0xffff0000, v112
	v_mov_b32_dpp v127, v113 row_shr:2 row_mask:0xf bank_mask:0xf
	v_mov_b32_dpp v123, v113 row_shr:1 row_mask:0xf bank_mask:0xf
	v_mul_f32_e32 v122, 0x45800000, v3
	v_cndmask_b32_e32 v124, v3, v122, vcc
	v_fmamk_f32 v3, v185, 0x3a800000, v224
	v_cmp_gt_f32_e32 vcc, s5, v3
	v_mul_f32_e32 v122, 0x4b800000, v3
	v_lshlrev_b32_e32 v174, 16, v127
	v_cndmask_b32_e32 v3, v3, v122, vcc
	v_rsq_f32_e32 v3, v3
	v_and_b32_e32 v175, 0xffff0000, v127
	v_lshlrev_b32_e32 v168, 16, v123
	v_and_b32_e32 v169, 0xffff0000, v123
	v_mul_f32_e32 v122, 0x45800000, v3
	v_cndmask_b32_e32 v122, v3, v122, vcc
	v_mov_b32_dpp v3, v116 row_ror:1 row_mask:0xf bank_mask:0xf bound_ctrl:1
	v_pk_mul_f32 v[96:97], v[96:97], v[128:129] op_sel_hi:[1,0]
	v_pk_fma_f32 v[174:175], v[150:151], v[174:175], v[162:163]
	v_mov_b32_dpp v3, v112 row_shr:1 row_mask:0xf bank_mask:0xf
	v_lshlrev_b32_e32 v116, 16, v3
	v_and_b32_e32 v117, 0xffff0000, v3
	v_pk_fma_f32 v[116:117], v[152:153], v[116:117], v[170:171]
	v_pk_fma_f32 v[168:169], v[154:155], v[168:169], v[174:175]
	v_pk_fma_f32 v[170:171], v[156:157], v[178:179], v[116:117]
	v_mov_b32_dpp v125, v118 row_ror:2 row_mask:0xf bank_mask:0xf bound_ctrl:1
	v_pk_mul_f32 v[116:117], v[170:171], s[30:31] op_sel_hi:[1,0]
	v_pk_mul_f32 v[170:171], v[170:171], 0.5 op_sel_hi:[1,0]
	v_med3_f32 v178, v116, s47, v225
	v_med3_f32 v179, v117, s47, v225
	v_pk_mul_f32 v[182:183], v[178:179], v[178:179]
	v_mov_b64_e32 v[116:117], s[36:37]
	v_pk_fma_f32 v[190:191], v[182:183], s[34:35], v[116:117] op_sel_hi:[1,0,0] neg_lo:[1,0,0] neg_hi:[1,0,0]
	v_pk_mul_f32 v[98:99], v[98:99], v[128:129] op_sel_hi:[1,0]
	v_pk_fma_f32 v[190:191], v[182:183], v[190:191], s[38:39] op_sel_hi:[1,1,0]
	v_mov_b32_dpp v3, v118 row_ror:1 row_mask:0xf bank_mask:0xf bound_ctrl:1
	v_pk_fma_f32 v[190:191], v[182:183], v[190:191], s[40:41] op_sel_hi:[1,1,0]
	v_mov_b32_dpp v125, v114 row_shr:2 row_mask:0xf bank_mask:0xf
	v_pk_fma_f32 v[190:191], v[182:183], v[190:191], s[42:43] op_sel_hi:[1,1,0]
	v_mov_b32_dpp v3, v114 row_shr:1 row_mask:0xf bank_mask:0xf
	v_pk_fma_f32 v[190:191], v[182:183], v[190:191], s[44:45] op_sel_hi:[1,1,0]
	v_mov_b32_dpp v127, v119 row_ror:2 row_mask:0xf bank_mask:0xf bound_ctrl:1
	v_pk_fma_f32 v[190:191], v[182:183], v[190:191], s[46:47] op_sel_hi:[1,1,0]
	v_mov_b32_dpp v123, v119 row_ror:1 row_mask:0xf bank_mask:0xf bound_ctrl:1
	v_pk_fma_f32 v[182:183], v[182:183], v[190:191], s[48:49] op_sel_hi:[1,1,0]
	v_mov_b32_dpp v127, v115 row_shr:2 row_mask:0xf bank_mask:0xf
	v_pk_mul_f32 v[178:179], v[178:179], v[182:183]
	v_mov_b32_dpp v123, v115 row_shr:1 row_mask:0xf bank_mask:0xf
	v_pk_fma_f32 v[170:171], v[170:171], v[178:179], v[170:171]
	v_lshlrev_b32_e32 v118, 16, v123
	v_pk_mul_f32 v[96:97], v[96:97], v[170:171]
	v_lshlrev_b32_e32 v170, 16, v113
	v_and_b32_e32 v171, 0xffff0000, v113
	v_pk_fma_f32 v[168:169], v[158:159], v[170:171], v[168:169]
	v_cvt_pk_bf16_f32 v96, v96, v97
	v_and_b32_e32 v119, 0xffff0000, v123
	v_pk_mul_f32 v[170:171], v[168:169], s[30:31] op_sel_hi:[1,0]
	v_pk_mul_f32 v[168:169], v[168:169], 0.5 op_sel_hi:[1,0]
	v_med3_f32 v170, v170, s47, v225
	v_med3_f32 v171, v171, s47, v225
	v_pk_mul_f32 v[174:175], v[170:171], v[170:171]
	v_pk_mul_f32 v[92:93], v[92:93], v[128:129] op_sel_hi:[1,0]
	v_pk_fma_f32 v[178:179], v[174:175], s[34:35], v[116:117] op_sel_hi:[1,0,0] neg_lo:[1,0,0] neg_hi:[1,0,0]
	v_mad_i64_i32 v[120:121], s[8:9], v1, s91, 0
	v_pk_fma_f32 v[178:179], v[174:175], v[178:179], s[38:39] op_sel_hi:[1,1,0]
	v_readlane_b32 s8, v240, 58
	v_pk_fma_f32 v[178:179], v[174:175], v[178:179], s[40:41] op_sel_hi:[1,1,0]
	v_readlane_b32 s9, v240, 59
	v_pk_fma_f32 v[178:179], v[174:175], v[178:179], s[42:43] op_sel_hi:[1,1,0]
	v_pk_mul_f32 v[94:95], v[94:95], v[128:129] op_sel_hi:[1,0]
	v_pk_fma_f32 v[178:179], v[174:175], v[178:179], s[44:45] op_sel_hi:[1,1,0]
	v_pk_mul_f32 v[88:89], v[88:89], v[126:127] op_sel_hi:[1,0]
	v_pk_fma_f32 v[178:179], v[174:175], v[178:179], s[46:47] op_sel_hi:[1,1,0]
	v_pk_mul_f32 v[90:91], v[90:91], v[126:127] op_sel_hi:[1,0]
	v_pk_fma_f32 v[174:175], v[174:175], v[178:179], s[48:49] op_sel_hi:[1,1,0]
	v_pk_mul_f32 v[84:85], v[84:85], v[126:127] op_sel_hi:[1,0]
	v_pk_mul_f32 v[170:171], v[170:171], v[174:175]
	v_lshlrev_b32_e32 v174, 16, v114
	v_pk_fma_f32 v[168:169], v[168:169], v[170:171], v[168:169]
	v_and_b32_e32 v175, 0xffff0000, v114
	v_pk_mul_f32 v[98:99], v[98:99], v[168:169]
	v_lshlrev_b32_e32 v168, 16, v125
; __device__ __forceinline__ unsigned cvt_pk_bf16(float lo, float hi) { unsigned r; asm volatile("v_cvt_pk_bf16_f32 %0, %1, %2" : "=v"(r) : "v"(lo), "v"(hi)); return r; }
;     static __device__ __forceinline__ u32x2 finish2(const float (&g0)[4], const float (&g1)[4], const float (&g2)[4], const float (&w0)[4], const float (&w1)[4], const float (&w2)[4], const float (&bb)[4],
;                                                     const f32x4 v, float rs) {
;         float h[4];
; #pragma unroll
;         for (int j = 0; j < 4; j += 2) {
;             const f32x2 gc = (f32x2){bb[j] + w0[j] * g2[j] + w1[j] * g1[j] + w2[j] * g0[j], bb[j + 1] + w0[j + 1] * g2[j + 1] + w1[j + 1] * g1[j + 1] + w2[j + 1] * g0[j + 1]};
;             const f32x2 ge = gelu_pk(gc) * ((f32x2){v[j], v[j + 1]} * rs); h[j] = ge.x; h[j + 1] = ge.y; }
;         u32x2 w; w.x = cvt_pk_bf16(h[0], h[1]); w.y = cvt_pk_bf16(h[2], h[3]); return w;
;     }
;     __device__ __forceinline__ void operator()(const f32x4 (&acc)[2][2][4][2], const Unit& u, int wr, int wc, int fr, int fq) const {
;     ...
;             for (int ai = 0; ai < 2; ++ai) { const int R0 = u.rb + ai * HALF + wr * 64; const bf16_t* gp = G + (size_t)(R0 + fr) * 2816 + col8;
;                 u32x4 gq[4], prv = (u32x4){0u, 0u, 0u, 0u};
; #pragma unroll
;                 for (int m = 0; m < 4; ++m) gq[m] = *(const u32x4*)(gp + (size_t)m * 16 * 2816);
;                 if ((R0 & 8191) != 0) prv = *(const u32x4*)(gp - (size_t)16 * 2816);
;                 u32x4 pv = prv;
; #pragma unroll
;                 for (int m = 0; m < 4; ++m) { const u32x4 cur = gq[m]; u32x4 hw;
; #pragma unroll
;                     for (int hv = 0; hv < 2; ++hv) { const u32x2 c2 = half2(cur, hv), p2 = half2(pv, hv);
;                         const u32x2 q1 = dpp_prev<1>(p2, c2), q2 = dpp_prev<2>(p2, c2);
;                         float g0[4], g1[4], g2[4]; unpk4(c2, g0); unpk4(q1, g1); unpk4(q2, g2);
;                         const u32x2 r = finish2(g0, g1, g2, w0[hv], w1[hv], w2[hv], bb[hv], acc[ai][bj][m][hv], rs8[ai][m]);
;                         if (hv == 0) { hw.x = r.x; hw.y = r.y; } else { hw.z = r.x; hw.w = r.y; } }
;                     *(u32x4*)(H + (size_t)(R0 + fr + 16 * m) * 2816 + col8) = hw;
;                     pv = cur; } }
	v_and_b32_e32 v169, 0xffff0000, v125
	v_cvt_pk_bf16_f32 v97, v98, v99
	v_lshlrev_b32_e32 v98, 16, v3
	v_and_b32_e32 v99, 0xffff0000, v3
	v_pk_fma_f32 v[168:169], v[132:133], v[168:169], v[144:145]
	v_lshlrev_b32_e32 v170, 16, v127
	v_pk_fma_f32 v[98:99], v[136:137], v[98:99], v[168:169]
	v_and_b32_e32 v171, 0xffff0000, v127
	v_pk_fma_f32 v[98:99], v[140:141], v[174:175], v[98:99]
	v_mov_b32_dpp v3, v112 row_ror:1 row_mask:0xf bank_mask:0xf bound_ctrl:1
	v_pk_mul_f32 v[168:169], v[98:99], s[30:31] op_sel_hi:[1,0]
	v_pk_mul_f32 v[98:99], v[98:99], 0.5 op_sel_hi:[1,0]
	v_med3_f32 v168, v168, s47, v225
	v_med3_f32 v169, v169, s47, v225
	v_pk_mul_f32 v[174:175], v[168:169], v[168:169]
	v_mov_b32_dpp v3, v108 row_shr:1 row_mask:0xf bank_mask:0xf
	v_pk_fma_f32 v[178:179], v[174:175], s[34:35], v[116:117] op_sel_hi:[1,0,0] neg_lo:[1,0,0] neg_hi:[1,0,0]
	v_pk_mul_f32 v[86:87], v[86:87], v[126:127] op_sel_hi:[1,0]
	v_pk_fma_f32 v[178:179], v[174:175], v[178:179], s[38:39] op_sel_hi:[1,1,0]
	v_pk_mul_f32 v[80:81], v[80:81], v[124:125] op_sel_hi:[1,0]
	v_pk_fma_f32 v[178:179], v[174:175], v[178:179], s[40:41] op_sel_hi:[1,1,0]
	v_pk_mul_f32 v[82:83], v[82:83], v[124:125] op_sel_hi:[1,0]
	v_pk_fma_f32 v[178:179], v[174:175], v[178:179], s[42:43] op_sel_hi:[1,1,0]
	v_pk_mul_f32 v[76:77], v[76:77], v[124:125] op_sel_hi:[1,0]
	v_pk_fma_f32 v[178:179], v[174:175], v[178:179], s[44:45] op_sel_hi:[1,1,0]
	v_pk_mul_f32 v[78:79], v[78:79], v[124:125] op_sel_hi:[1,0]
	v_pk_fma_f32 v[178:179], v[174:175], v[178:179], s[46:47] op_sel_hi:[1,1,0]
	v_pk_mul_f32 v[72:73], v[72:73], v[122:123] op_sel_hi:[1,0]
	v_pk_fma_f32 v[174:175], v[174:175], v[178:179], s[48:49] op_sel_hi:[1,1,0]
	v_pk_mul_f32 v[74:75], v[74:75], v[122:123] op_sel_hi:[1,0]
	v_pk_mul_f32 v[168:169], v[168:169], v[174:175]
	v_pk_mul_f32 v[64:65], v[64:65], v[122:123] op_sel_hi:[1,0]
	v_pk_fma_f32 v[98:99], v[98:99], v[168:169], v[98:99]
	v_pk_fma_f32 v[168:169], v[134:135], v[170:171], v[146:147]
	v_pk_mul_f32 v[92:93], v[92:93], v[98:99]
	v_lshlrev_b32_e32 v98, 16, v115
	v_and_b32_e32 v99, 0xffff0000, v115
	v_pk_fma_f32 v[118:119], v[138:139], v[118:119], v[168:169]
	v_pk_mul_f32 v[66:67], v[66:67], v[122:123] op_sel_hi:[1,0]
	v_pk_fma_f32 v[98:99], v[142:143], v[98:99], v[118:119]
	v_readlane_b32 s52, v240, 62
	v_pk_mul_f32 v[118:119], v[98:99], s[30:31] op_sel_hi:[1,0]
	v_pk_mul_f32 v[98:99], v[98:99], 0.5 op_sel_hi:[1,0]
	v_med3_f32 v118, v118, s47, v225
	v_med3_f32 v119, v119, s47, v225
	v_pk_mul_f32 v[168:169], v[118:119], v[118:119]
	v_readlane_b32 s66, v239, 12
	v_pk_fma_f32 v[170:171], v[168:169], s[34:35], v[116:117] op_sel_hi:[1,0,0] neg_lo:[1,0,0] neg_hi:[1,0,0]
	v_readlane_b32 s67, v239, 13
	v_pk_fma_f32 v[170:171], v[168:169], v[170:171], s[38:39] op_sel_hi:[1,1,0]
	v_readlane_b32 s53, v240, 63
	v_pk_fma_f32 v[170:171], v[168:169], v[170:171], s[40:41] op_sel_hi:[1,1,0]
	v_readlane_b32 s54, v239, 0
	v_pk_fma_f32 v[170:171], v[168:169], v[170:171], s[42:43] op_sel_hi:[1,1,0]
	v_readlane_b32 s55, v239, 1
	v_pk_fma_f32 v[170:171], v[168:169], v[170:171], s[44:45] op_sel_hi:[1,1,0]
	v_readlane_b32 s56, v239, 2
	v_pk_fma_f32 v[170:171], v[168:169], v[170:171], s[46:47] op_sel_hi:[1,1,0]
	v_readlane_b32 s57, v239, 3
	v_pk_fma_f32 v[168:169], v[168:169], v[170:171], s[48:49] op_sel_hi:[1,1,0]
	v_readlane_b32 s58, v239, 4
	v_pk_mul_f32 v[118:119], v[118:119], v[168:169]
	v_lshl_add_u64 v[168:169], s[8:9], 0, v[120:121]
	v_pk_fma_f32 v[98:99], v[98:99], v[118:119], v[98:99]
	v_mov_b32_e32 v120, 0
	v_pk_mul_f32 v[94:95], v[94:95], v[98:99]
	v_cvt_pk_bf16_f32 v98, v92, v93
	v_lshl_add_u64 v[92:93], v[168:169], 0, v[180:181]
	v_cvt_pk_bf16_f32 v99, v94, v95
	global_store_dwordx4 v[92:93], v[96:99], off sc1
	v_lshlrev_b32_e32 v92, 16, v3
	v_and_b32_e32 v93, 0xffff0000, v3
	v_mov_b32_dpp v97, v112 row_ror:2 row_mask:0xf bank_mask:0xf bound_ctrl:1
	v_mov_b32_dpp v95, v113 row_ror:1 row_mask:0xf bank_mask:0xf bound_ctrl:1
	v_mov_b32_dpp v99, v113 row_ror:2 row_mask:0xf bank_mask:0xf bound_ctrl:1
	v_mov_b32_dpp v97, v108 row_shr:2 row_mask:0xf bank_mask:0xf
	v_lshlrev_b32_e32 v96, 16, v97
	v_and_b32_e32 v97, 0xffff0000, v97
	v_pk_fma_f32 v[96:97], v[148:149], v[96:97], v[160:161]
	v_lshlrev_b32_e32 v112, 16, v108
	v_and_b32_e32 v113, 0xffff0000, v108
	v_pk_fma_f32 v[92:93], v[152:153], v[92:93], v[96:97]
	v_mov_b32_dpp v99, v109 row_shr:2 row_mask:0xf bank_mask:0xf
	v_pk_fma_f32 v[92:93], v[156:157], v[112:113], v[92:93]
	v_mov_b32_dpp v95, v109 row_shr:1 row_mask:0xf bank_mask:0xf
	v_pk_mul_f32 v[96:97], v[92:93], s[30:31] op_sel_hi:[1,0]
	v_lshlrev_b32_e32 v98, 16, v99
	v_med3_f32 v96, v96, s47, v225
	v_med3_f32 v97, v97, s47, v225
	v_pk_mul_f32 v[112:113], v[96:97], v[96:97]
	v_and_b32_e32 v99, 0xffff0000, v99
	v_pk_fma_f32 v[118:119], v[112:113], s[34:35], v[116:117] op_sel_hi:[1,0,0] neg_lo:[1,0,0] neg_hi:[1,0,0]
	v_pk_mul_f32 v[92:93], v[92:93], 0.5 op_sel_hi:[1,0]
	v_pk_fma_f32 v[118:119], v[112:113], v[118:119], s[38:39] op_sel_hi:[1,1,0]
	v_lshlrev_b32_e32 v94, 16, v95
	v_pk_fma_f32 v[118:119], v[112:113], v[118:119], s[40:41] op_sel_hi:[1,1,0]
	v_and_b32_e32 v95, 0xffff0000, v95
	v_pk_fma_f32 v[118:119], v[112:113], v[118:119], s[42:43] op_sel_hi:[1,1,0]
	v_mov_b32_dpp v3, v114 row_ror:1 row_mask:0xf bank_mask:0xf bound_ctrl:1
	v_pk_fma_f32 v[118:119], v[112:113], v[118:119], s[44:45] op_sel_hi:[1,1,0]
	v_mov_b32_e32 v121, 0
	v_pk_fma_f32 v[118:119], v[112:113], v[118:119], s[46:47] op_sel_hi:[1,1,0]
	v_mov_b32_dpp v3, v110 row_shr:1 row_mask:0xf bank_mask:0xf
	v_pk_fma_f32 v[112:113], v[112:113], v[118:119], s[48:49] op_sel_hi:[1,1,0]
	v_mov_b32_e32 v118, 0
	v_pk_mul_f32 v[96:97], v[96:97], v[112:113]
; __device__ __forceinline__ unsigned cvt_pk_bf16(float lo, float hi) { unsigned r; asm volatile("v_cvt_pk_bf16_f32 %0, %1, %2" : "=v"(r) : "v"(lo), "v"(hi)); return r; }
;     static __device__ __forceinline__ u32x2 finish2(const float (&g0)[4], const float (&g1)[4], const float (&g2)[4], const float (&w0)[4], const float (&w1)[4], const float (&w2)[4], const float (&bb)[4],
;                                                     const f32x4 v, float rs) {
;         float h[4];
; #pragma unroll
;         for (int j = 0; j < 4; j += 2) {
;             const f32x2 gc = (f32x2){bb[j] + w0[j] * g2[j] + w1[j] * g1[j] + w2[j] * g0[j], bb[j + 1] + w0[j + 1] * g2[j + 1] + w1[j + 1] * g1[j + 1] + w2[j + 1] * g0[j + 1]};
;             const f32x2 ge = gelu_pk(gc) * ((f32x2){v[j], v[j + 1]} * rs); h[j] = ge.x; h[j + 1] = ge.y; }
;         u32x2 w; w.x = cvt_pk_bf16(h[0], h[1]); w.y = cvt_pk_bf16(h[2], h[3]); return w;
;     }
;     __device__ __forceinline__ void operator()(const f32x4 (&acc)[2][2][4][2], const Unit& u, int wr, int wc, int fr, int fq) const {
;     ...
;             for (int ai = 0; ai < 2; ++ai) { const int R0 = u.rb + ai * HALF + wr * 64; const bf16_t* gp = G + (size_t)(R0 + fr) * 2816 + col8;
;                 u32x4 gq[4], prv = (u32x4){0u, 0u, 0u, 0u};
; #pragma unroll
;                 for (int m = 0; m < 4; ++m) gq[m] = *(const u32x4*)(gp + (size_t)m * 16 * 2816);
;                 if ((R0 & 8191) != 0) prv = *(const u32x4*)(gp - (size_t)16 * 2816);
;                 u32x4 pv = prv;
; #pragma unroll
;                 for (int m = 0; m < 4; ++m) { const u32x4 cur = gq[m]; u32x4 hw;
; #pragma unroll
;                     for (int hv = 0; hv < 2; ++hv) { const u32x2 c2 = half2(cur, hv), p2 = half2(pv, hv);
;                         const u32x2 q1 = dpp_prev<1>(p2, c2), q2 = dpp_prev<2>(p2, c2);
;                         float g0[4], g1[4], g2[4]; unpk4(c2, g0); unpk4(q1, g1); unpk4(q2, g2);
;                         const u32x2 r = finish2(g0, g1, g2, w0[hv], w1[hv], w2[hv], bb[hv], acc[ai][bj][m][hv], rs8[ai][m]);
;                         if (hv == 0) { hw.x = r.x; hw.y = r.y; } else { hw.z = r.x; hw.w = r.y; } }
;                     *(u32x4*)(H + (size_t)(R0 + fr + 16 * m) * 2816 + col8) = hw;
;                     pv = cur; } }
	v_mov_b32_e32 v119, 0
	v_pk_fma_f32 v[92:93], v[92:93], v[96:97], v[92:93]
	v_pk_fma_f32 v[96:97], v[150:151], v[98:99], v[162:163]
	v_pk_mul_f32 v[88:89], v[88:89], v[92:93]
	v_lshlrev_b32_e32 v92, 16, v109
	v_and_b32_e32 v93, 0xffff0000, v109
	v_pk_fma_f32 v[94:95], v[154:155], v[94:95], v[96:97]
	v_cvt_pk_bf16_f32 v88, v88, v89
	v_readlane_b32 s59, v239, 5
	v_pk_fma_f32 v[92:93], v[158:159], v[92:93], v[94:95]
	v_readlane_b32 s60, v239, 6
	v_pk_mul_f32 v[94:95], v[92:93], s[30:31] op_sel_hi:[1,0]
	v_pk_mul_f32 v[92:93], v[92:93], 0.5 op_sel_hi:[1,0]
	v_med3_f32 v94, v94, s47, v225
	v_med3_f32 v95, v95, s47, v225
	v_pk_mul_f32 v[96:97], v[94:95], v[94:95]
	v_readlane_b32 s61, v239, 7
	v_pk_fma_f32 v[98:99], v[96:97], s[34:35], v[116:117] op_sel_hi:[1,0,0] neg_lo:[1,0,0] neg_hi:[1,0,0]
	v_readlane_b32 s62, v239, 8
	v_pk_fma_f32 v[98:99], v[96:97], v[98:99], s[38:39] op_sel_hi:[1,1,0]
	v_readlane_b32 s63, v239, 9
	v_pk_fma_f32 v[98:99], v[96:97], v[98:99], s[40:41] op_sel_hi:[1,1,0]
	v_readlane_b32 s64, v239, 10
	v_pk_fma_f32 v[98:99], v[96:97], v[98:99], s[42:43] op_sel_hi:[1,1,0]
	v_readlane_b32 s65, v239, 11
	v_pk_fma_f32 v[98:99], v[96:97], v[98:99], s[44:45] op_sel_hi:[1,1,0]
	s_nop 0
	v_pk_fma_f32 v[98:99], v[96:97], v[98:99], s[46:47] op_sel_hi:[1,1,0]
	s_nop 0
	v_pk_fma_f32 v[96:97], v[96:97], v[98:99], s[48:49] op_sel_hi:[1,1,0]
	v_lshlrev_b32_e32 v98, 16, v110
	v_pk_mul_f32 v[94:95], v[94:95], v[96:97]
	v_and_b32_e32 v99, 0xffff0000, v110
	v_pk_fma_f32 v[92:93], v[92:93], v[94:95], v[92:93]
	v_mov_b32_dpp v95, v114 row_ror:2 row_mask:0xf bank_mask:0xf bound_ctrl:1
	v_pk_mul_f32 v[90:91], v[90:91], v[92:93]
	v_mov_b32_dpp v97, v115 row_ror:2 row_mask:0xf bank_mask:0xf bound_ctrl:1
	v_mov_b32_dpp v95, v110 row_shr:2 row_mask:0xf bank_mask:0xf
	v_lshlrev_b32_e32 v94, 16, v95
	v_and_b32_e32 v95, 0xffff0000, v95
	v_cvt_pk_bf16_f32 v89, v90, v91
	v_lshlrev_b32_e32 v90, 16, v3
	v_and_b32_e32 v91, 0xffff0000, v3
	v_pk_fma_f32 v[94:95], v[132:133], v[94:95], v[144:145]
	v_mov_b32_dpp v93, v115 row_ror:1 row_mask:0xf bank_mask:0xf bound_ctrl:1
	v_pk_fma_f32 v[90:91], v[136:137], v[90:91], v[94:95]
	v_mov_b32_dpp v97, v111 row_shr:2 row_mask:0xf bank_mask:0xf
	v_pk_fma_f32 v[90:91], v[140:141], v[98:99], v[90:91]
	v_mov_b32_dpp v93, v111 row_shr:1 row_mask:0xf bank_mask:0xf
	v_pk_mul_f32 v[94:95], v[90:91], s[30:31] op_sel_hi:[1,0]
	v_lshlrev_b32_e32 v96, 16, v97
	v_med3_f32 v94, v94, s47, v225
	v_med3_f32 v95, v95, s47, v225
	v_pk_mul_f32 v[98:99], v[94:95], v[94:95]
	v_and_b32_e32 v97, 0xffff0000, v97
	v_pk_fma_f32 v[112:113], v[98:99], s[34:35], v[116:117] op_sel_hi:[1,0,0] neg_lo:[1,0,0] neg_hi:[1,0,0]
	v_pk_mul_f32 v[90:91], v[90:91], 0.5 op_sel_hi:[1,0]
	v_pk_fma_f32 v[112:113], v[98:99], v[112:113], s[38:39] op_sel_hi:[1,1,0]
	v_lshlrev_b32_e32 v92, 16, v93
	v_pk_fma_f32 v[112:113], v[98:99], v[112:113], s[40:41] op_sel_hi:[1,1,0]
	v_and_b32_e32 v93, 0xffff0000, v93
	v_pk_fma_f32 v[112:113], v[98:99], v[112:113], s[42:43] op_sel_hi:[1,1,0]
	v_add_u32_e32 v3, 16, v1
	v_pk_fma_f32 v[112:113], v[98:99], v[112:113], s[44:45] op_sel_hi:[1,1,0]
	s_nop 0
	v_pk_fma_f32 v[112:113], v[98:99], v[112:113], s[46:47] op_sel_hi:[1,1,0]
	s_nop 0
	v_pk_fma_f32 v[98:99], v[98:99], v[112:113], s[48:49] op_sel_hi:[1,1,0]
	s_nop 0
	v_pk_mul_f32 v[94:95], v[94:95], v[98:99]
	s_nop 0
	v_pk_fma_f32 v[90:91], v[90:91], v[94:95], v[90:91]
	v_pk_fma_f32 v[94:95], v[134:135], v[96:97], v[146:147]
	v_pk_mul_f32 v[84:85], v[84:85], v[90:91]
	v_lshlrev_b32_e32 v90, 16, v111
	v_and_b32_e32 v91, 0xffff0000, v111
	v_pk_fma_f32 v[92:93], v[138:139], v[92:93], v[94:95]
	s_nop 0
	v_pk_fma_f32 v[90:91], v[142:143], v[90:91], v[92:93]
	s_nop 0
	v_pk_mul_f32 v[92:93], v[90:91], s[30:31] op_sel_hi:[1,0]
	v_pk_mul_f32 v[90:91], v[90:91], 0.5 op_sel_hi:[1,0]
	v_med3_f32 v92, v92, s47, v225
	v_med3_f32 v93, v93, s47, v225
	v_pk_mul_f32 v[94:95], v[92:93], v[92:93]
	s_nop 0
	v_pk_fma_f32 v[96:97], v[94:95], s[34:35], v[116:117] op_sel_hi:[1,0,0] neg_lo:[1,0,0] neg_hi:[1,0,0]
	s_nop 0
	v_pk_fma_f32 v[96:97], v[94:95], v[96:97], s[38:39] op_sel_hi:[1,1,0]
	s_nop 0
	v_pk_fma_f32 v[96:97], v[94:95], v[96:97], s[40:41] op_sel_hi:[1,1,0]
	s_nop 0
	v_pk_fma_f32 v[96:97], v[94:95], v[96:97], s[42:43] op_sel_hi:[1,1,0]
	s_nop 0
	v_pk_fma_f32 v[96:97], v[94:95], v[96:97], s[44:45] op_sel_hi:[1,1,0]
	s_nop 0
	v_pk_fma_f32 v[96:97], v[94:95], v[96:97], s[46:47] op_sel_hi:[1,1,0]
	s_nop 0
	v_pk_fma_f32 v[94:95], v[94:95], v[96:97], s[48:49] op_sel_hi:[1,1,0]
	s_nop 0
	v_pk_mul_f32 v[92:93], v[92:93], v[94:95]
	v_lshlrev_b32_e32 v94, 16, v104
	v_pk_fma_f32 v[90:91], v[90:91], v[92:93], v[90:91]
	v_and_b32_e32 v95, 0xffff0000, v104
	v_pk_mul_f32 v[86:87], v[86:87], v[90:91]
	v_cvt_pk_bf16_f32 v90, v84, v85
	v_mov_b64_e32 v[84:85], s[8:9]
	v_mad_i64_i32 v[170:171], s[8:9], v3, s91, v[84:85]
	v_cvt_pk_bf16_f32 v91, v86, v87
	v_lshl_add_u64 v[86:87], v[170:171], 0, v[180:181]
	global_store_dwordx4 v[86:87], v[88:91], off sc1
	v_mov_b32_dpp v3, v108 row_ror:1 row_mask:0xf bank_mask:0xf bound_ctrl:1
	v_mov_b32_dpp v93, v109 row_ror:2 row_mask:0xf bank_mask:0xf bound_ctrl:1
	v_mov_b32_dpp v91, v108 row_ror:2 row_mask:0xf bank_mask:0xf bound_ctrl:1
	v_mov_b32_dpp v3, v104 row_shr:1 row_mask:0xf bank_mask:0xf
	v_lshlrev_b32_e32 v86, 16, v3
	v_mov_b32_dpp v91, v104 row_shr:2 row_mask:0xf bank_mask:0xf
	v_lshlrev_b32_e32 v90, 16, v91
	v_and_b32_e32 v91, 0xffff0000, v91
	v_and_b32_e32 v87, 0xffff0000, v3
	v_pk_fma_f32 v[90:91], v[148:149], v[90:91], v[160:161]
	v_mov_b32_dpp v89, v109 row_ror:1 row_mask:0xf bank_mask:0xf bound_ctrl:1
	v_pk_fma_f32 v[86:87], v[152:153], v[86:87], v[90:91]
; __device__ __forceinline__ unsigned cvt_pk_bf16(float lo, float hi) { unsigned r; asm volatile("v_cvt_pk_bf16_f32 %0, %1, %2" : "=v"(r) : "v"(lo), "v"(hi)); return r; }
;     static __device__ __forceinline__ u32x2 finish2(const float (&g0)[4], const float (&g1)[4], const float (&g2)[4], const float (&w0)[4], const float (&w1)[4], const float (&w2)[4], const float (&bb)[4],
;                                                     const f32x4 v, float rs) {
;         float h[4];
; #pragma unroll
;         for (int j = 0; j < 4; j += 2) {
;             const f32x2 gc = (f32x2){bb[j] + w0[j] * g2[j] + w1[j] * g1[j] + w2[j] * g0[j], bb[j + 1] + w0[j + 1] * g2[j + 1] + w1[j + 1] * g1[j + 1] + w2[j + 1] * g0[j + 1]};
;             const f32x2 ge = gelu_pk(gc) * ((f32x2){v[j], v[j + 1]} * rs); h[j] = ge.x; h[j + 1] = ge.y; }
;         u32x2 w; w.x = cvt_pk_bf16(h[0], h[1]); w.y = cvt_pk_bf16(h[2], h[3]); return w;
;     }
;     __device__ __forceinline__ void operator()(const f32x4 (&acc)[2][2][4][2], const Unit& u, int wr, int wc, int fr, int fq) const {
;     ...
;             for (int ai = 0; ai < 2; ++ai) { const int R0 = u.rb + ai * HALF + wr * 64; const bf16_t* gp = G + (size_t)(R0 + fr) * 2816 + col8;
;                 u32x4 gq[4], prv = (u32x4){0u, 0u, 0u, 0u};
; #pragma unroll
;                 for (int m = 0; m < 4; ++m) gq[m] = *(const u32x4*)(gp + (size_t)m * 16 * 2816);
;                 if ((R0 & 8191) != 0) prv = *(const u32x4*)(gp - (size_t)16 * 2816);
;                 u32x4 pv = prv;
; #pragma unroll
;                 for (int m = 0; m < 4; ++m) { const u32x4 cur = gq[m]; u32x4 hw;
; #pragma unroll
;                     for (int hv = 0; hv < 2; ++hv) { const u32x2 c2 = half2(cur, hv), p2 = half2(pv, hv);
;                         const u32x2 q1 = dpp_prev<1>(p2, c2), q2 = dpp_prev<2>(p2, c2);
;                         float g0[4], g1[4], g2[4]; unpk4(c2, g0); unpk4(q1, g1); unpk4(q2, g2);
;                         const u32x2 r = finish2(g0, g1, g2, w0[hv], w1[hv], w2[hv], bb[hv], acc[ai][bj][m][hv], rs8[ai][m]);
;                         if (hv == 0) { hw.x = r.x; hw.y = r.y; } else { hw.z = r.x; hw.w = r.y; } }
;                     *(u32x4*)(H + (size_t)(R0 + fr + 16 * m) * 2816 + col8) = hw;
;                     pv = cur; } }
	v_mov_b32_dpp v93, v105 row_shr:2 row_mask:0xf bank_mask:0xf
	v_pk_fma_f32 v[86:87], v[156:157], v[94:95], v[86:87]
	v_mov_b32_dpp v89, v105 row_shr:1 row_mask:0xf bank_mask:0xf
	v_pk_mul_f32 v[90:91], v[86:87], s[30:31] op_sel_hi:[1,0]
	v_lshlrev_b32_e32 v92, 16, v93
	v_med3_f32 v90, v90, s47, v225
	v_med3_f32 v91, v91, s47, v225
	v_pk_mul_f32 v[94:95], v[90:91], v[90:91]
	v_and_b32_e32 v93, 0xffff0000, v93
	v_pk_fma_f32 v[96:97], v[94:95], s[34:35], v[116:117] op_sel_hi:[1,0,0] neg_lo:[1,0,0] neg_hi:[1,0,0]
	v_pk_mul_f32 v[86:87], v[86:87], 0.5 op_sel_hi:[1,0]
	v_pk_fma_f32 v[96:97], v[94:95], v[96:97], s[38:39] op_sel_hi:[1,1,0]
	v_lshlrev_b32_e32 v88, 16, v89
	v_pk_fma_f32 v[96:97], v[94:95], v[96:97], s[40:41] op_sel_hi:[1,1,0]
	v_and_b32_e32 v89, 0xffff0000, v89
	v_pk_fma_f32 v[96:97], v[94:95], v[96:97], s[42:43] op_sel_hi:[1,1,0]
	v_mov_b32_dpp v3, v110 row_ror:1 row_mask:0xf bank_mask:0xf bound_ctrl:1
	v_pk_fma_f32 v[96:97], v[94:95], v[96:97], s[44:45] op_sel_hi:[1,1,0]
	s_nop 0
	v_pk_fma_f32 v[96:97], v[94:95], v[96:97], s[46:47] op_sel_hi:[1,1,0]
	v_mov_b32_dpp v3, v106 row_shr:1 row_mask:0xf bank_mask:0xf
	v_pk_fma_f32 v[94:95], v[94:95], v[96:97], s[48:49] op_sel_hi:[1,1,0]
	s_nop 0
	v_pk_mul_f32 v[90:91], v[90:91], v[94:95]
	s_nop 0
	v_pk_fma_f32 v[86:87], v[86:87], v[90:91], v[86:87]
	v_pk_fma_f32 v[90:91], v[150:151], v[92:93], v[162:163]
	v_pk_mul_f32 v[80:81], v[80:81], v[86:87]
	v_lshlrev_b32_e32 v86, 16, v105
	v_and_b32_e32 v87, 0xffff0000, v105
	v_pk_fma_f32 v[88:89], v[154:155], v[88:89], v[90:91]
	v_cvt_pk_bf16_f32 v80, v80, v81
	s_nop 0
	v_pk_fma_f32 v[86:87], v[158:159], v[86:87], v[88:89]
	s_nop 0
	v_pk_mul_f32 v[88:89], v[86:87], s[30:31] op_sel_hi:[1,0]
	v_pk_mul_f32 v[86:87], v[86:87], 0.5 op_sel_hi:[1,0]
	v_med3_f32 v88, v88, s47, v225
	v_med3_f32 v89, v89, s47, v225
	v_pk_mul_f32 v[90:91], v[88:89], v[88:89]
	s_nop 0
	v_pk_fma_f32 v[92:93], v[90:91], s[34:35], v[116:117] op_sel_hi:[1,0,0] neg_lo:[1,0,0] neg_hi:[1,0,0]
	s_nop 0
	v_pk_fma_f32 v[92:93], v[90:91], v[92:93], s[38:39] op_sel_hi:[1,1,0]
	s_nop 0
	v_pk_fma_f32 v[92:93], v[90:91], v[92:93], s[40:41] op_sel_hi:[1,1,0]
	s_nop 0
	v_pk_fma_f32 v[92:93], v[90:91], v[92:93], s[42:43] op_sel_hi:[1,1,0]
	s_nop 0
	v_pk_fma_f32 v[92:93], v[90:91], v[92:93], s[44:45] op_sel_hi:[1,1,0]
	s_nop 0
	v_pk_fma_f32 v[92:93], v[90:91], v[92:93], s[46:47] op_sel_hi:[1,1,0]
	s_nop 0
	v_pk_fma_f32 v[90:91], v[90:91], v[92:93], s[48:49] op_sel_hi:[1,1,0]
	v_lshlrev_b32_e32 v92, 16, v106
	v_pk_mul_f32 v[88:89], v[88:89], v[90:91]
	v_and_b32_e32 v93, 0xffff0000, v106
	v_pk_fma_f32 v[86:87], v[86:87], v[88:89], v[86:87]
	v_mov_b32_dpp v89, v110 row_ror:2 row_mask:0xf bank_mask:0xf bound_ctrl:1
	v_pk_mul_f32 v[82:83], v[82:83], v[86:87]
	v_mov_b32_dpp v91, v111 row_ror:2 row_mask:0xf bank_mask:0xf bound_ctrl:1
	v_mov_b32_dpp v89, v106 row_shr:2 row_mask:0xf bank_mask:0xf
	v_lshlrev_b32_e32 v88, 16, v89
	v_and_b32_e32 v89, 0xffff0000, v89
	v_cvt_pk_bf16_f32 v81, v82, v83
	v_lshlrev_b32_e32 v82, 16, v3
	v_and_b32_e32 v83, 0xffff0000, v3
	v_pk_fma_f32 v[88:89], v[132:133], v[88:89], v[144:145]
	v_mov_b32_dpp v87, v111 row_ror:1 row_mask:0xf bank_mask:0xf bound_ctrl:1
	v_pk_fma_f32 v[82:83], v[136:137], v[82:83], v[88:89]
	v_mov_b32_dpp v91, v107 row_shr:2 row_mask:0xf bank_mask:0xf
	v_pk_fma_f32 v[82:83], v[140:141], v[92:93], v[82:83]
	v_mov_b32_dpp v87, v107 row_shr:1 row_mask:0xf bank_mask:0xf
	v_pk_mul_f32 v[88:89], v[82:83], s[30:31] op_sel_hi:[1,0]
	v_lshlrev_b32_e32 v90, 16, v91
	v_med3_f32 v88, v88, s47, v225
	v_med3_f32 v89, v89, s47, v225
	v_pk_mul_f32 v[92:93], v[88:89], v[88:89]
	v_and_b32_e32 v91, 0xffff0000, v91
	v_pk_fma_f32 v[94:95], v[92:93], s[34:35], v[116:117] op_sel_hi:[1,0,0] neg_lo:[1,0,0] neg_hi:[1,0,0]
	v_pk_mul_f32 v[82:83], v[82:83], 0.5 op_sel_hi:[1,0]
	v_pk_fma_f32 v[94:95], v[92:93], v[94:95], s[38:39] op_sel_hi:[1,1,0]
	v_lshlrev_b32_e32 v86, 16, v87
	v_pk_fma_f32 v[94:95], v[92:93], v[94:95], s[40:41] op_sel_hi:[1,1,0]
	v_and_b32_e32 v87, 0xffff0000, v87
	v_pk_fma_f32 v[94:95], v[92:93], v[94:95], s[42:43] op_sel_hi:[1,1,0]
	v_add_u32_e32 v3, 32, v1
	v_pk_fma_f32 v[94:95], v[92:93], v[94:95], s[44:45] op_sel_hi:[1,1,0]
	v_mad_i64_i32 v[174:175], s[8:9], v3, s91, v[84:85]
	v_pk_fma_f32 v[94:95], v[92:93], v[94:95], s[46:47] op_sel_hi:[1,1,0]
	v_mov_b32_dpp v3, v104 row_ror:1 row_mask:0xf bank_mask:0xf bound_ctrl:1
	v_pk_fma_f32 v[92:93], v[92:93], v[94:95], s[48:49] op_sel_hi:[1,1,0]
	v_add_u32_e32 v1, 48, v1
	v_pk_mul_f32 v[88:89], v[88:89], v[92:93]
	v_mov_b32_dpp v3, v100 row_shr:1 row_mask:0xf bank_mask:0xf
	v_pk_fma_f32 v[82:83], v[82:83], v[88:89], v[82:83]
	v_pk_fma_f32 v[88:89], v[134:135], v[90:91], v[146:147]
	v_pk_mul_f32 v[76:77], v[76:77], v[82:83]
	v_lshlrev_b32_e32 v82, 16, v107
	v_and_b32_e32 v83, 0xffff0000, v107
	v_pk_fma_f32 v[86:87], v[138:139], v[86:87], v[88:89]
	s_nop 0
	v_pk_fma_f32 v[82:83], v[142:143], v[82:83], v[86:87]
	s_nop 0
	v_pk_mul_f32 v[86:87], v[82:83], s[30:31] op_sel_hi:[1,0]
	v_pk_mul_f32 v[82:83], v[82:83], 0.5 op_sel_hi:[1,0]
	v_med3_f32 v86, v86, s47, v225
	v_med3_f32 v87, v87, s47, v225
	v_pk_mul_f32 v[88:89], v[86:87], v[86:87]
	s_nop 0
	v_pk_fma_f32 v[90:91], v[88:89], s[34:35], v[116:117] op_sel_hi:[1,0,0] neg_lo:[1,0,0] neg_hi:[1,0,0]
	s_nop 0
	v_pk_fma_f32 v[90:91], v[88:89], v[90:91], s[38:39] op_sel_hi:[1,1,0]
	s_nop 0
	v_pk_fma_f32 v[90:91], v[88:89], v[90:91], s[40:41] op_sel_hi:[1,1,0]
	s_nop 0
	v_pk_fma_f32 v[90:91], v[88:89], v[90:91], s[42:43] op_sel_hi:[1,1,0]
	s_nop 0
	v_pk_fma_f32 v[90:91], v[88:89], v[90:91], s[44:45] op_sel_hi:[1,1,0]
	s_nop 0
	v_pk_fma_f32 v[90:91], v[88:89], v[90:91], s[46:47] op_sel_hi:[1,1,0]
; __device__ __forceinline__ unsigned cvt_pk_bf16(float lo, float hi) { unsigned r; asm volatile("v_cvt_pk_bf16_f32 %0, %1, %2" : "=v"(r) : "v"(lo), "v"(hi)); return r; }
;     static __device__ __forceinline__ u32x2 finish2(const float (&g0)[4], const float (&g1)[4], const float (&g2)[4], const float (&w0)[4], const float (&w1)[4], const float (&w2)[4], const float (&bb)[4],
;                                                     const f32x4 v, float rs) {
;         float h[4];
; #pragma unroll
;         for (int j = 0; j < 4; j += 2) {
;             const f32x2 gc = (f32x2){bb[j] + w0[j] * g2[j] + w1[j] * g1[j] + w2[j] * g0[j], bb[j + 1] + w0[j + 1] * g2[j + 1] + w1[j + 1] * g1[j + 1] + w2[j + 1] * g0[j + 1]};
;             const f32x2 ge = gelu_pk(gc) * ((f32x2){v[j], v[j + 1]} * rs); h[j] = ge.x; h[j + 1] = ge.y; }
;         u32x2 w; w.x = cvt_pk_bf16(h[0], h[1]); w.y = cvt_pk_bf16(h[2], h[3]); return w;
;     }
;     __device__ __forceinline__ void operator()(const f32x4 (&acc)[2][2][4][2], const Unit& u, int wr, int wc, int fr, int fq) const {
;     ...
;             for (int ai = 0; ai < 2; ++ai) { const int R0 = u.rb + ai * HALF + wr * 64; const bf16_t* gp = G + (size_t)(R0 + fr) * 2816 + col8;
;                 u32x4 gq[4], prv = (u32x4){0u, 0u, 0u, 0u};
; #pragma unroll
;                 for (int m = 0; m < 4; ++m) gq[m] = *(const u32x4*)(gp + (size_t)m * 16 * 2816);
;                 if ((R0 & 8191) != 0) prv = *(const u32x4*)(gp - (size_t)16 * 2816);
;                 u32x4 pv = prv;
; #pragma unroll
;                 for (int m = 0; m < 4; ++m) { const u32x4 cur = gq[m]; u32x4 hw;
; #pragma unroll
;                     for (int hv = 0; hv < 2; ++hv) { const u32x2 c2 = half2(cur, hv), p2 = half2(pv, hv);
;                         const u32x2 q1 = dpp_prev<1>(p2, c2), q2 = dpp_prev<2>(p2, c2);
;                         float g0[4], g1[4], g2[4]; unpk4(c2, g0); unpk4(q1, g1); unpk4(q2, g2);
;                         const u32x2 r = finish2(g0, g1, g2, w0[hv], w1[hv], w2[hv], bb[hv], acc[ai][bj][m][hv], rs8[ai][m]);
;                         if (hv == 0) { hw.x = r.x; hw.y = r.y; } else { hw.z = r.x; hw.w = r.y; } }
;                     *(u32x4*)(H + (size_t)(R0 + fr + 16 * m) * 2816 + col8) = hw;
;                     pv = cur; } }
	s_nop 0
	v_pk_fma_f32 v[88:89], v[88:89], v[90:91], s[48:49] op_sel_hi:[1,1,0]
	s_nop 0
	v_pk_mul_f32 v[86:87], v[86:87], v[88:89]
	s_nop 0
	v_pk_fma_f32 v[82:83], v[82:83], v[86:87], v[82:83]
	v_lshlrev_b32_e32 v86, 16, v100
	v_pk_mul_f32 v[78:79], v[78:79], v[82:83]
	v_cvt_pk_bf16_f32 v82, v76, v77
	v_lshl_add_u64 v[76:77], v[174:175], 0, v[180:181]
	v_cvt_pk_bf16_f32 v83, v78, v79
	global_store_dwordx4 v[76:77], v[80:83], off sc1
	v_lshlrev_b32_e32 v76, 16, v3
	v_and_b32_e32 v77, 0xffff0000, v3
	v_mov_b32_dpp v81, v104 row_ror:2 row_mask:0xf bank_mask:0xf bound_ctrl:1
	v_and_b32_e32 v87, 0xffff0000, v100
	v_mov_b32_dpp v83, v105 row_ror:2 row_mask:0xf bank_mask:0xf bound_ctrl:1
	v_mov_b32_dpp v81, v100 row_shr:2 row_mask:0xf bank_mask:0xf
	v_lshlrev_b32_e32 v80, 16, v81
	v_and_b32_e32 v81, 0xffff0000, v81
	v_pk_fma_f32 v[80:81], v[148:149], v[80:81], v[160:161]
	v_mov_b32_dpp v79, v105 row_ror:1 row_mask:0xf bank_mask:0xf bound_ctrl:1
	v_pk_fma_f32 v[76:77], v[152:153], v[76:77], v[80:81]
	v_mov_b32_dpp v83, v101 row_shr:2 row_mask:0xf bank_mask:0xf
	v_pk_fma_f32 v[76:77], v[156:157], v[86:87], v[76:77]
	v_mov_b32_dpp v79, v101 row_shr:1 row_mask:0xf bank_mask:0xf
	v_pk_mul_f32 v[80:81], v[76:77], s[30:31] op_sel_hi:[1,0]
	v_lshlrev_b32_e32 v82, 16, v83
	v_med3_f32 v80, v80, s47, v225
	v_med3_f32 v81, v81, s47, v225
	v_pk_mul_f32 v[86:87], v[80:81], v[80:81]
	v_and_b32_e32 v83, 0xffff0000, v83
	v_pk_fma_f32 v[88:89], v[86:87], s[34:35], v[116:117] op_sel_hi:[1,0,0] neg_lo:[1,0,0] neg_hi:[1,0,0]
	v_pk_mul_f32 v[76:77], v[76:77], 0.5 op_sel_hi:[1,0]
	v_pk_fma_f32 v[88:89], v[86:87], v[88:89], s[38:39] op_sel_hi:[1,1,0]
	v_lshlrev_b32_e32 v78, 16, v79
	v_pk_fma_f32 v[88:89], v[86:87], v[88:89], s[40:41] op_sel_hi:[1,1,0]
	v_and_b32_e32 v79, 0xffff0000, v79
	v_pk_fma_f32 v[88:89], v[86:87], v[88:89], s[42:43] op_sel_hi:[1,1,0]
	v_mov_b32_dpp v3, v106 row_ror:1 row_mask:0xf bank_mask:0xf bound_ctrl:1
	v_pk_fma_f32 v[88:89], v[86:87], v[88:89], s[44:45] op_sel_hi:[1,1,0]
	s_nop 0
	v_pk_fma_f32 v[88:89], v[86:87], v[88:89], s[46:47] op_sel_hi:[1,1,0]
	v_mov_b32_dpp v3, v102 row_shr:1 row_mask:0xf bank_mask:0xf
	v_pk_fma_f32 v[86:87], v[86:87], v[88:89], s[48:49] op_sel_hi:[1,1,0]
	s_nop 0
	v_pk_mul_f32 v[80:81], v[80:81], v[86:87]
	s_nop 0
	v_pk_fma_f32 v[76:77], v[76:77], v[80:81], v[76:77]
	v_pk_fma_f32 v[80:81], v[150:151], v[82:83], v[162:163]
	v_pk_mul_f32 v[72:73], v[72:73], v[76:77]
	v_lshlrev_b32_e32 v76, 16, v101
	v_and_b32_e32 v77, 0xffff0000, v101
	v_pk_fma_f32 v[78:79], v[154:155], v[78:79], v[80:81]
	v_cvt_pk_bf16_f32 v72, v72, v73
	s_nop 0
	v_pk_fma_f32 v[76:77], v[158:159], v[76:77], v[78:79]
	s_nop 0
	v_pk_mul_f32 v[78:79], v[76:77], s[30:31] op_sel_hi:[1,0]
	v_pk_mul_f32 v[76:77], v[76:77], 0.5 op_sel_hi:[1,0]
	v_med3_f32 v78, v78, s47, v225
	v_med3_f32 v79, v79, s47, v225
	v_pk_mul_f32 v[80:81], v[78:79], v[78:79]
	s_nop 0
	v_pk_fma_f32 v[82:83], v[80:81], s[34:35], v[116:117] op_sel_hi:[1,0,0] neg_lo:[1,0,0] neg_hi:[1,0,0]
	s_nop 0
	v_pk_fma_f32 v[82:83], v[80:81], v[82:83], s[38:39] op_sel_hi:[1,1,0]
	s_nop 0
	v_pk_fma_f32 v[82:83], v[80:81], v[82:83], s[40:41] op_sel_hi:[1,1,0]
	s_nop 0
	v_pk_fma_f32 v[82:83], v[80:81], v[82:83], s[42:43] op_sel_hi:[1,1,0]
	s_nop 0
	v_pk_fma_f32 v[82:83], v[80:81], v[82:83], s[44:45] op_sel_hi:[1,1,0]
	s_nop 0
	v_pk_fma_f32 v[82:83], v[80:81], v[82:83], s[46:47] op_sel_hi:[1,1,0]
	s_nop 0
	v_pk_fma_f32 v[80:81], v[80:81], v[82:83], s[48:49] op_sel_hi:[1,1,0]
	v_lshlrev_b32_e32 v82, 16, v102
	v_pk_mul_f32 v[78:79], v[78:79], v[80:81]
	v_and_b32_e32 v83, 0xffff0000, v102
	v_pk_fma_f32 v[76:77], v[76:77], v[78:79], v[76:77]
	v_mov_b32_dpp v79, v106 row_ror:2 row_mask:0xf bank_mask:0xf bound_ctrl:1
	v_pk_mul_f32 v[74:75], v[74:75], v[76:77]
	v_mov_b32_dpp v81, v107 row_ror:2 row_mask:0xf bank_mask:0xf bound_ctrl:1
	v_mov_b32_dpp v79, v102 row_shr:2 row_mask:0xf bank_mask:0xf
	v_lshlrev_b32_e32 v78, 16, v79
	v_and_b32_e32 v79, 0xffff0000, v79
	v_cvt_pk_bf16_f32 v73, v74, v75
	v_lshlrev_b32_e32 v74, 16, v3
	v_and_b32_e32 v75, 0xffff0000, v3
	v_pk_fma_f32 v[78:79], v[132:133], v[78:79], v[144:145]
	v_mov_b32_dpp v77, v107 row_ror:1 row_mask:0xf bank_mask:0xf bound_ctrl:1
	v_pk_fma_f32 v[74:75], v[136:137], v[74:75], v[78:79]
	v_mov_b32_dpp v81, v103 row_shr:2 row_mask:0xf bank_mask:0xf
	v_pk_fma_f32 v[74:75], v[140:141], v[82:83], v[74:75]
	v_mov_b32_dpp v77, v103 row_shr:1 row_mask:0xf bank_mask:0xf
	v_pk_mul_f32 v[78:79], v[74:75], s[30:31] op_sel_hi:[1,0]
	v_lshlrev_b32_e32 v80, 16, v81
	v_med3_f32 v78, v78, s47, v225
	v_med3_f32 v79, v79, s47, v225
	v_pk_mul_f32 v[82:83], v[78:79], v[78:79]
	v_and_b32_e32 v81, 0xffff0000, v81
	v_pk_fma_f32 v[86:87], v[82:83], s[34:35], v[116:117] op_sel_hi:[1,0,0] neg_lo:[1,0,0] neg_hi:[1,0,0]
	v_pk_mul_f32 v[74:75], v[74:75], 0.5 op_sel_hi:[1,0]
	v_pk_fma_f32 v[86:87], v[82:83], v[86:87], s[38:39] op_sel_hi:[1,1,0]
	v_lshlrev_b32_e32 v76, 16, v77
	v_pk_fma_f32 v[86:87], v[82:83], v[86:87], s[40:41] op_sel_hi:[1,1,0]
	v_and_b32_e32 v77, 0xffff0000, v77
	v_pk_fma_f32 v[86:87], v[82:83], v[86:87], s[42:43] op_sel_hi:[1,1,0]
	v_mad_i64_i32 v[132:133], s[8:9], v1, s91, v[84:85]
	v_pk_fma_f32 v[86:87], v[82:83], v[86:87], s[44:45] op_sel_hi:[1,1,0]
	v_readlane_b32 s8, v240, 19
	v_pk_fma_f32 v[86:87], v[82:83], v[86:87], s[46:47] op_sel_hi:[1,1,0]
	v_readlane_b32 s9, v240, 20
	v_pk_fma_f32 v[82:83], v[82:83], v[86:87], s[48:49] op_sel_hi:[1,1,0]
	s_nop 0
	v_pk_mul_f32 v[78:79], v[78:79], v[82:83]
	s_nop 0
	v_pk_fma_f32 v[74:75], v[74:75], v[78:79], v[74:75]
	v_pk_fma_f32 v[78:79], v[134:135], v[80:81], v[146:147]
	v_pk_mul_f32 v[64:65], v[64:65], v[74:75]
;     static __device__ __forceinline__ u32x2 finish2(const float (&g0)[4], const float (&g1)[4], const float (&g2)[4], const float (&w0)[4], const float (&w1)[4], const float (&w2)[4], const float (&bb)[4],
;                                                     const f32x4 v, float rs) {
;         float h[4];
; #pragma unroll
;         for (int j = 0; j < 4; j += 2) {
;             const f32x2 gc = (f32x2){bb[j] + w0[j] * g2[j] + w1[j] * g1[j] + w2[j] * g0[j], bb[j + 1] + w0[j + 1] * g2[j + 1] + w1[j + 1] * g1[j + 1] + w2[j + 1] * g0[j + 1]};
;             const f32x2 ge = gelu_pk(gc) * ((f32x2){v[j], v[j + 1]} * rs); h[j] = ge.x; h[j + 1] = ge.y; }
;         u32x2 w; w.x = cvt_pk_bf16(h[0], h[1]); w.y = cvt_pk_bf16(h[2], h[3]); return w;
;     }
;     __device__ __forceinline__ void operator()(const f32x4 (&acc)[2][2][4][2], const Unit& u, int wr, int wc, int fr, int fq) const {
;     ...
;             for (int hv = 0; hv < 2; ++hv) { ld4f(cw + col8 + 4 * hv, w0[hv]); ld4f(cw + 2816 + col8 + 4 * hv, w1[hv]); ld4f(cw + 2 * 2816 + col8 + 4 * hv, w2[hv]); ld4f(cb + col8 + 4 * hv, bb[hv]); }
; #pragma unroll
;             for (int ai = 0; ai < 2; ++ai) { const int R0 = u.rb + ai * HALF + wr * 64; const bf16_t* gp = G + (size_t)(R0 + fr) * 2816 + col8;
;                 u32x4 gq[4], prv = (u32x4){0u, 0u, 0u, 0u};
; #pragma unroll
;                 for (int m = 0; m < 4; ++m) gq[m] = *(const u32x4*)(gp + (size_t)m * 16 * 2816);
;                 if ((R0 & 8191) != 0) prv = *(const u32x4*)(gp - (size_t)16 * 2816);
;                 u32x4 pv = prv;
; #pragma unroll
;                 for (int m = 0; m < 4; ++m) { const u32x4 cur = gq[m]; u32x4 hw;
; #pragma unroll
;                     for (int hv = 0; hv < 2; ++hv) { const u32x2 c2 = half2(cur, hv), p2 = half2(pv, hv);
;                         const u32x2 q1 = dpp_prev<1>(p2, c2), q2 = dpp_prev<2>(p2, c2);
;                         float g0[4], g1[4], g2[4]; unpk4(c2, g0); unpk4(q1, g1); unpk4(q2, g2);
;                         const u32x2 r = finish2(g0, g1, g2, w0[hv], w1[hv], w2[hv], bb[hv], acc[ai][bj][m][hv], rs8[ai][m]);
;                         if (hv == 0) { hw.x = r.x; hw.y = r.y; } else { hw.z = r.x; hw.w = r.y; } }
;                     *(u32x4*)(H + (size_t)(R0 + fr + 16 * m) * 2816 + col8) = hw;
;                     pv = cur; } }
	v_lshlrev_b32_e32 v74, 16, v103
	v_and_b32_e32 v75, 0xffff0000, v103
	v_pk_fma_f32 v[76:77], v[138:139], v[76:77], v[78:79]
	v_add_u32_e32 v134, 0x80, v212
	v_pk_fma_f32 v[74:75], v[142:143], v[74:75], v[76:77]
	v_ashrrev_i32_e32 v135, 31, v134
	v_pk_mul_f32 v[76:77], v[74:75], s[30:31] op_sel_hi:[1,0]
	v_pk_mul_f32 v[74:75], v[74:75], 0.5 op_sel_hi:[1,0]
	v_med3_f32 v76, v76, s47, v225
	v_med3_f32 v77, v77, s47, v225
	v_pk_mul_f32 v[78:79], v[76:77], v[76:77]
	v_lshl_add_u64 v[136:137], v[134:135], 1, v[214:215]
	v_pk_fma_f32 v[80:81], v[78:79], s[34:35], v[116:117] op_sel_hi:[1,0,0] neg_lo:[1,0,0] neg_hi:[1,0,0]
	v_add_co_u32_e32 v100, vcc, s10, v136
	v_pk_fma_f32 v[80:81], v[78:79], v[80:81], s[38:39] op_sel_hi:[1,1,0]
	s_nop 0
	v_addc_co_u32_e32 v101, vcc, 0, v137, vcc
	v_pk_fma_f32 v[80:81], v[78:79], v[80:81], s[40:41] op_sel_hi:[1,1,0]
	s_nop 0
	v_pk_fma_f32 v[80:81], v[78:79], v[80:81], s[42:43] op_sel_hi:[1,1,0]
	s_nop 0
	v_pk_fma_f32 v[80:81], v[78:79], v[80:81], s[44:45] op_sel_hi:[1,1,0]
	s_nop 0
	v_pk_fma_f32 v[80:81], v[78:79], v[80:81], s[46:47] op_sel_hi:[1,1,0]
	s_nop 0
	v_pk_fma_f32 v[78:79], v[78:79], v[80:81], s[48:49] op_sel_hi:[1,1,0]
	s_nop 0
	v_pk_mul_f32 v[76:77], v[76:77], v[78:79]
	s_nop 0
	v_pk_fma_f32 v[74:75], v[74:75], v[76:77], v[74:75]
	s_nop 0
	v_pk_mul_f32 v[66:67], v[66:67], v[74:75]
	v_cvt_pk_bf16_f32 v74, v64, v65
	v_lshl_add_u64 v[64:65], v[132:133], 0, v[180:181]
	v_cvt_pk_bf16_f32 v75, v66, v67
	global_store_dwordx4 v[64:65], v[72:75], off sc1
	v_lshlrev_b64 v[64:65], 2, v[134:135]
	v_lshl_add_u64 v[76:77], s[8:9], 0, v[64:65]
	v_readlane_b32 s8, v240, 21
	v_readlane_b32 s9, v240, 22
	v_lshl_add_u64 v[72:73], s[66:67], 0, v[64:65]
	v_lshl_add_u64 v[96:97], s[88:89], 0, v[64:65]
	v_lshl_add_u64 v[80:81], s[8:9], 0, v[64:65]
	global_load_dwordx4 v[64:67], v[72:73], off offset:16
	global_load_dwordx4 v[84:87], v[72:73], off
	s_nop 0
	global_load_dwordx4 v[72:75], v[76:77], off offset:16
	global_load_dwordx4 v[88:91], v[76:77], off
	s_nop 0
	global_load_dwordx4 v[76:79], v[80:81], off offset:16
	global_load_dwordx4 v[92:95], v[80:81], off
	s_nop 0
	global_load_dwordx4 v[80:83], v[96:97], off offset:16
	s_nop 0
	global_load_dwordx4 v[96:99], v[96:97], off
	s_nop 0
	global_load_dwordx4 v[114:117], v[136:137], off
	global_load_dwordx4 v[110:113], v[100:101], off
	v_add_co_u32_e32 v100, vcc, 0x2c000, v136
	s_nop 1
	v_addc_co_u32_e32 v101, vcc, 0, v137, vcc
	global_load_dwordx4 v[106:109], v[100:101], off
	v_add_co_u32_e32 v100, vcc, 0x42000, v136
	s_nop 1
	v_addc_co_u32_e32 v101, vcc, 0, v137, vcc
	global_load_dwordx4 v[102:105], v[100:101], off
	v_mov_b32_e32 v100, 0
	s_andn2_b64 vcc, exec, s[0:1]
	s_cbranch_vccnz .LBB0_1018
	v_add_co_u32_e32 v118, vcc, 0xfffea000, v136
	s_nop 1
	v_addc_co_u32_e32 v119, vcc, -1, v137, vcc
	global_load_dwordx4 v[118:121], v[118:119], off
.LBB0_1018:
	s_waitcnt vmcnt(0)
	s_nop 0
	v_mov_b32_dpp v123, v118 row_ror:2 row_mask:0xf bank_mask:0xf bound_ctrl:1
	v_mov_b32_dpp v1, v118 row_ror:1 row_mask:0xf bank_mask:0xf bound_ctrl:1
	v_mov_b32_dpp v101, v119 row_ror:1 row_mask:0xf bank_mask:0xf bound_ctrl:1
	v_mov_b32_dpp v123, v114 row_shr:2 row_mask:0xf bank_mask:0xf
	v_mov_b32_dpp v1, v114 row_shr:1 row_mask:0xf bank_mask:0xf
	v_lshlrev_b32_e32 v138, 16, v123
	v_and_b32_e32 v139, 0xffff0000, v123
	v_mov_b32_dpp v125, v119 row_ror:2 row_mask:0xf bank_mask:0xf bound_ctrl:1
	v_lshlrev_b32_e32 v118, 16, v1
	v_and_b32_e32 v119, 0xffff0000, v1
	v_pk_fma_f32 v[138:139], v[84:85], v[138:139], v[96:97]
	v_lshlrev_b32_e32 v142, 16, v114
	v_and_b32_e32 v143, 0xffff0000, v114
	v_pk_fma_f32 v[118:119], v[88:89], v[118:119], v[138:139]
	v_mov_b32_dpp v125, v115 row_shr:2 row_mask:0xf bank_mask:0xf
	v_pk_fma_f32 v[138:139], v[92:93], v[142:143], v[118:119]
	v_mov_b32_e32 v189, v188
	v_pk_mul_f32 v[118:119], v[138:139], s[30:31] op_sel_hi:[1,0]
	v_mov_b32_dpp v101, v115 row_shr:1 row_mask:0xf bank_mask:0xf
	v_med3_f32 v142, v118, s47, v225
	v_med3_f32 v143, v119, s47, v225
	v_pk_mul_f32 v[144:145], v[142:143], v[142:143]
	v_mov_b64_e32 v[118:119], s[36:37]
	v_pk_fma_f32 v[146:147], v[144:145], s[34:35], v[118:119] op_sel_hi:[1,0,0] neg_lo:[1,0,0] neg_hi:[1,0,0]
	v_lshlrev_b32_e32 v140, 16, v125
	v_pk_fma_f32 v[146:147], v[144:145], v[146:147], s[38:39] op_sel_hi:[1,1,0]
	v_and_b32_e32 v141, 0xffff0000, v125
	v_pk_fma_f32 v[146:147], v[144:145], v[146:147], s[40:41] op_sel_hi:[1,1,0]
	v_pk_mul_f32 v[138:139], v[138:139], 0.5 op_sel_hi:[1,0]
	v_pk_fma_f32 v[146:147], v[144:145], v[146:147], s[42:43] op_sel_hi:[1,1,0]
	v_lshlrev_b32_e32 v136, 16, v101
	v_pk_fma_f32 v[146:147], v[144:145], v[146:147], s[44:45] op_sel_hi:[1,1,0]
	v_and_b32_e32 v137, 0xffff0000, v101
	v_pk_fma_f32 v[146:147], v[144:145], v[146:147], s[46:47] op_sel_hi:[1,1,0]
	v_pk_mul_f32 v[68:69], v[68:69], v[188:189]
	v_pk_fma_f32 v[144:145], v[144:145], v[146:147], s[48:49] op_sel_hi:[1,1,0]
	v_pk_fma_f32 v[140:141], v[86:87], v[140:141], v[98:99]
	v_pk_mul_f32 v[142:143], v[142:143], v[144:145]
	v_pk_fma_f32 v[136:137], v[90:91], v[136:137], v[140:141]
	v_pk_fma_f32 v[138:139], v[138:139], v[142:143], v[138:139]
	v_mov_b32_dpp v123, v120 row_ror:2 row_mask:0xf bank_mask:0xf bound_ctrl:1
	v_pk_mul_f32 v[68:69], v[68:69], v[138:139]
	v_lshlrev_b32_e32 v138, 16, v115
	v_and_b32_e32 v139, 0xffff0000, v115
	v_pk_fma_f32 v[136:137], v[94:95], v[138:139], v[136:137]
	v_pk_mul_f32 v[70:71], v[70:71], v[188:189]
	v_pk_mul_f32 v[138:139], v[136:137], s[30:31] op_sel_hi:[1,0]
	v_pk_mul_f32 v[136:137], v[136:137], 0.5 op_sel_hi:[1,0]
	v_med3_f32 v138, v138, s47, v225
	v_med3_f32 v139, v139, s47, v225
	v_pk_mul_f32 v[140:141], v[138:139], v[138:139]
; __device__ __forceinline__ unsigned cvt_pk_bf16(float lo, float hi) { unsigned r; asm volatile("v_cvt_pk_bf16_f32 %0, %1, %2" : "=v"(r) : "v"(lo), "v"(hi)); return r; }
;     static __device__ __forceinline__ u32x2 finish2(const float (&g0)[4], const float (&g1)[4], const float (&g2)[4], const float (&w0)[4], const float (&w1)[4], const float (&w2)[4], const float (&bb)[4],
;                                                     const f32x4 v, float rs) {
;         float h[4];
; #pragma unroll
;         for (int j = 0; j < 4; j += 2) {
;             const f32x2 gc = (f32x2){bb[j] + w0[j] * g2[j] + w1[j] * g1[j] + w2[j] * g0[j], bb[j + 1] + w0[j + 1] * g2[j + 1] + w1[j + 1] * g1[j + 1] + w2[j + 1] * g0[j + 1]};
;             const f32x2 ge = gelu_pk(gc) * ((f32x2){v[j], v[j + 1]} * rs); h[j] = ge.x; h[j + 1] = ge.y; }
;         u32x2 w; w.x = cvt_pk_bf16(h[0], h[1]); w.y = cvt_pk_bf16(h[2], h[3]); return w;
;     }
;     __device__ __forceinline__ void operator()(const f32x4 (&acc)[2][2][4][2], const Unit& u, int wr, int wc, int fr, int fq) const {
;     ...
;             for (int ai = 0; ai < 2; ++ai) { const int R0 = u.rb + ai * HALF + wr * 64; const bf16_t* gp = G + (size_t)(R0 + fr) * 2816 + col8;
;                 u32x4 gq[4], prv = (u32x4){0u, 0u, 0u, 0u};
; #pragma unroll
;                 for (int m = 0; m < 4; ++m) gq[m] = *(const u32x4*)(gp + (size_t)m * 16 * 2816);
;                 if ((R0 & 8191) != 0) prv = *(const u32x4*)(gp - (size_t)16 * 2816);
;                 u32x4 pv = prv;
; #pragma unroll
;                 for (int m = 0; m < 4; ++m) { const u32x4 cur = gq[m]; u32x4 hw;
; #pragma unroll
;                     for (int hv = 0; hv < 2; ++hv) { const u32x2 c2 = half2(cur, hv), p2 = half2(pv, hv);
;                         const u32x2 q1 = dpp_prev<1>(p2, c2), q2 = dpp_prev<2>(p2, c2);
;                         float g0[4], g1[4], g2[4]; unpk4(c2, g0); unpk4(q1, g1); unpk4(q2, g2);
;                         const u32x2 r = finish2(g0, g1, g2, w0[hv], w1[hv], w2[hv], bb[hv], acc[ai][bj][m][hv], rs8[ai][m]);
;                         if (hv == 0) { hw.x = r.x; hw.y = r.y; } else { hw.z = r.x; hw.w = r.y; } }
;                     *(u32x4*)(H + (size_t)(R0 + fr + 16 * m) * 2816 + col8) = hw;
;                     pv = cur; } }
	v_mov_b32_dpp v1, v120 row_ror:1 row_mask:0xf bank_mask:0xf bound_ctrl:1
	v_pk_fma_f32 v[142:143], v[140:141], s[34:35], v[118:119] op_sel_hi:[1,0,0] neg_lo:[1,0,0] neg_hi:[1,0,0]
	v_mov_b32_dpp v123, v116 row_shr:2 row_mask:0xf bank_mask:0xf
	v_pk_fma_f32 v[142:143], v[140:141], v[142:143], s[38:39] op_sel_hi:[1,1,0]
	v_mov_b32_dpp v1, v116 row_shr:1 row_mask:0xf bank_mask:0xf
	v_pk_fma_f32 v[142:143], v[140:141], v[142:143], s[40:41] op_sel_hi:[1,1,0]
	v_cvt_pk_bf16_f32 v68, v68, v69
	v_mov_b32_dpp v125, v121 row_ror:2 row_mask:0xf bank_mask:0xf bound_ctrl:1
	v_pk_fma_f32 v[142:143], v[140:141], v[142:143], s[42:43] op_sel_hi:[1,1,0]
	v_mov_b32_dpp v101, v121 row_ror:1 row_mask:0xf bank_mask:0xf bound_ctrl:1
	v_pk_fma_f32 v[142:143], v[140:141], v[142:143], s[44:45] op_sel_hi:[1,1,0]
	v_mov_b32_dpp v125, v117 row_shr:2 row_mask:0xf bank_mask:0xf
	v_pk_fma_f32 v[142:143], v[140:141], v[142:143], s[46:47] op_sel_hi:[1,1,0]
	v_mov_b32_dpp v101, v117 row_shr:1 row_mask:0xf bank_mask:0xf
	v_pk_fma_f32 v[140:141], v[140:141], v[142:143], s[48:49] op_sel_hi:[1,1,0]
	v_lshlrev_b32_e32 v120, 16, v101
	v_pk_mul_f32 v[138:139], v[138:139], v[140:141]
	v_lshlrev_b32_e32 v140, 16, v116
	v_pk_fma_f32 v[136:137], v[136:137], v[138:139], v[136:137]
	v_and_b32_e32 v141, 0xffff0000, v116
	v_pk_mul_f32 v[70:71], v[70:71], v[136:137]
	v_lshlrev_b32_e32 v136, 16, v123
	v_and_b32_e32 v137, 0xffff0000, v123
	v_cvt_pk_bf16_f32 v69, v70, v71
	v_lshlrev_b32_e32 v70, 16, v1
	v_and_b32_e32 v71, 0xffff0000, v1
	v_pk_fma_f32 v[136:137], v[64:65], v[136:137], v[80:81]
	v_lshlrev_b32_e32 v138, 16, v125
	v_pk_fma_f32 v[70:71], v[72:73], v[70:71], v[136:137]
	v_and_b32_e32 v139, 0xffff0000, v125
	v_pk_fma_f32 v[70:71], v[76:77], v[140:141], v[70:71]
	v_and_b32_e32 v121, 0xffff0000, v101
	v_pk_mul_f32 v[136:137], v[70:71], s[30:31] op_sel_hi:[1,0]
	v_pk_mul_f32 v[70:71], v[70:71], 0.5 op_sel_hi:[1,0]
	v_med3_f32 v136, v136, s47, v225
	v_med3_f32 v137, v137, s47, v225
	v_pk_mul_f32 v[140:141], v[136:137], v[136:137]
	v_pk_mul_f32 v[60:61], v[60:61], v[188:189]
	v_pk_fma_f32 v[142:143], v[140:141], s[34:35], v[118:119] op_sel_hi:[1,0,0] neg_lo:[1,0,0] neg_hi:[1,0,0]
	v_pk_mul_f32 v[62:63], v[62:63], v[188:189]
	v_pk_fma_f32 v[142:143], v[140:141], v[142:143], s[38:39] op_sel_hi:[1,1,0]
	v_mov_b32_dpp v1, v114 row_ror:1 row_mask:0xf bank_mask:0xf bound_ctrl:1
	v_pk_fma_f32 v[142:143], v[140:141], v[142:143], s[40:41] op_sel_hi:[1,1,0]
	v_mov_b32_dpp v101, v115 row_ror:2 row_mask:0xf bank_mask:0xf bound_ctrl:1
	v_pk_fma_f32 v[142:143], v[140:141], v[142:143], s[42:43] op_sel_hi:[1,1,0]
	v_mov_b32_dpp v1, v110 row_shr:1 row_mask:0xf bank_mask:0xf
	v_pk_fma_f32 v[142:143], v[140:141], v[142:143], s[44:45] op_sel_hi:[1,1,0]
	v_mov_b32_dpp v101, v111 row_shr:2 row_mask:0xf bank_mask:0xf
	v_pk_fma_f32 v[142:143], v[140:141], v[142:143], s[46:47] op_sel_hi:[1,1,0]
	v_mov_b32_e32 v187, v186
	v_pk_fma_f32 v[140:141], v[140:141], v[142:143], s[48:49] op_sel_hi:[1,1,0]
	v_pk_mul_f32 v[56:57], v[56:57], v[186:187]
	v_pk_mul_f32 v[136:137], v[136:137], v[140:141]
	v_pk_mul_f32 v[58:59], v[58:59], v[186:187]
	v_pk_fma_f32 v[70:71], v[70:71], v[136:137], v[70:71]
	v_pk_fma_f32 v[136:137], v[66:67], v[138:139], v[82:83]
	v_pk_mul_f32 v[60:61], v[60:61], v[70:71]
	v_lshlrev_b32_e32 v70, 16, v117
	v_and_b32_e32 v71, 0xffff0000, v117
	v_pk_fma_f32 v[120:121], v[74:75], v[120:121], v[136:137]
	v_pk_mul_f32 v[52:53], v[52:53], v[186:187]
	v_pk_fma_f32 v[70:71], v[78:79], v[70:71], v[120:121]
	v_pk_mul_f32 v[54:55], v[54:55], v[186:187]
	v_pk_mul_f32 v[120:121], v[70:71], s[30:31] op_sel_hi:[1,0]
	v_pk_mul_f32 v[70:71], v[70:71], 0.5 op_sel_hi:[1,0]
	v_med3_f32 v120, v120, s47, v225
	v_med3_f32 v121, v121, s47, v225
	v_pk_mul_f32 v[136:137], v[120:121], v[120:121]
	v_mov_b32_e32 v185, v184
	v_pk_fma_f32 v[138:139], v[136:137], s[34:35], v[118:119] op_sel_hi:[1,0,0] neg_lo:[1,0,0] neg_hi:[1,0,0]
	v_pk_mul_f32 v[48:49], v[48:49], v[184:185]
	v_pk_fma_f32 v[138:139], v[136:137], v[138:139], s[38:39] op_sel_hi:[1,1,0]
	v_pk_mul_f32 v[50:51], v[50:51], v[184:185]
	v_pk_fma_f32 v[138:139], v[136:137], v[138:139], s[40:41] op_sel_hi:[1,1,0]
	v_pk_mul_f32 v[44:45], v[44:45], v[184:185]
	v_pk_fma_f32 v[138:139], v[136:137], v[138:139], s[42:43] op_sel_hi:[1,1,0]
	v_pk_mul_f32 v[46:47], v[46:47], v[184:185]
	v_pk_fma_f32 v[138:139], v[136:137], v[138:139], s[44:45] op_sel_hi:[1,1,0]
	v_mov_b32_e32 v3, v2
	v_pk_fma_f32 v[138:139], v[136:137], v[138:139], s[46:47] op_sel_hi:[1,1,0]
	v_pk_mul_f32 v[40:41], v[40:41], v[2:3]
	v_pk_fma_f32 v[136:137], v[136:137], v[138:139], s[48:49] op_sel_hi:[1,1,0]
	v_pk_mul_f32 v[42:43], v[42:43], v[2:3]
	v_pk_mul_f32 v[120:121], v[120:121], v[136:137]
	v_pk_mul_f32 v[36:37], v[36:37], v[2:3]
	v_pk_fma_f32 v[70:71], v[70:71], v[120:121], v[70:71]
	v_lshlrev_b32_e32 v120, 16, v110
	v_pk_mul_f32 v[62:63], v[62:63], v[70:71]
	v_cvt_pk_bf16_f32 v70, v60, v61
	v_lshlrev_b64 v[60:61], 1, v[134:135]
	v_cvt_pk_bf16_f32 v71, v62, v63
	v_lshl_add_u64 v[62:63], v[130:131], 0, v[60:61]
	global_store_dwordx4 v[62:63], v[68:71], off sc1
	v_lshlrev_b32_e32 v62, 16, v1
	v_and_b32_e32 v63, 0xffff0000, v1
	v_mov_b32_dpp v71, v114 row_ror:2 row_mask:0xf bank_mask:0xf bound_ctrl:1
	v_and_b32_e32 v121, 0xffff0000, v110
	v_mov_b32_dpp v69, v115 row_ror:1 row_mask:0xf bank_mask:0xf bound_ctrl:1
	v_mov_b32_dpp v71, v110 row_shr:2 row_mask:0xf bank_mask:0xf
	v_lshlrev_b32_e32 v70, 16, v71
	v_and_b32_e32 v71, 0xffff0000, v71
	v_pk_fma_f32 v[70:71], v[84:85], v[70:71], v[96:97]
	v_mov_b32_dpp v69, v111 row_shr:1 row_mask:0xf bank_mask:0xf
	v_pk_fma_f32 v[62:63], v[88:89], v[62:63], v[70:71]
; __device__ __forceinline__ unsigned cvt_pk_bf16(float lo, float hi) { unsigned r; asm volatile("v_cvt_pk_bf16_f32 %0, %1, %2" : "=v"(r) : "v"(lo), "v"(hi)); return r; }
;     static __device__ __forceinline__ u32x2 finish2(const float (&g0)[4], const float (&g1)[4], const float (&g2)[4], const float (&w0)[4], const float (&w1)[4], const float (&w2)[4], const float (&bb)[4],
;                                                     const f32x4 v, float rs) {
;         float h[4];
; #pragma unroll
;         for (int j = 0; j < 4; j += 2) {
;             const f32x2 gc = (f32x2){bb[j] + w0[j] * g2[j] + w1[j] * g1[j] + w2[j] * g0[j], bb[j + 1] + w0[j + 1] * g2[j + 1] + w1[j + 1] * g1[j + 1] + w2[j + 1] * g0[j + 1]};
;             const f32x2 ge = gelu_pk(gc) * ((f32x2){v[j], v[j + 1]} * rs); h[j] = ge.x; h[j + 1] = ge.y; }
;         u32x2 w; w.x = cvt_pk_bf16(h[0], h[1]); w.y = cvt_pk_bf16(h[2], h[3]); return w;
;     }
;     __device__ __forceinline__ void operator()(const f32x4 (&acc)[2][2][4][2], const Unit& u, int wr, int wc, int fr, int fq) const {
;     ...
;             for (int ai = 0; ai < 2; ++ai) { const int R0 = u.rb + ai * HALF + wr * 64; const bf16_t* gp = G + (size_t)(R0 + fr) * 2816 + col8;
;                 u32x4 gq[4], prv = (u32x4){0u, 0u, 0u, 0u};
; #pragma unroll
;                 for (int m = 0; m < 4; ++m) gq[m] = *(const u32x4*)(gp + (size_t)m * 16 * 2816);
;                 if ((R0 & 8191) != 0) prv = *(const u32x4*)(gp - (size_t)16 * 2816);
;                 u32x4 pv = prv;
; #pragma unroll
;                 for (int m = 0; m < 4; ++m) { const u32x4 cur = gq[m]; u32x4 hw;
; #pragma unroll
;                     for (int hv = 0; hv < 2; ++hv) { const u32x2 c2 = half2(cur, hv), p2 = half2(pv, hv);
;                         const u32x2 q1 = dpp_prev<1>(p2, c2), q2 = dpp_prev<2>(p2, c2);
;                         float g0[4], g1[4], g2[4]; unpk4(c2, g0); unpk4(q1, g1); unpk4(q2, g2);
;                         const u32x2 r = finish2(g0, g1, g2, w0[hv], w1[hv], w2[hv], bb[hv], acc[ai][bj][m][hv], rs8[ai][m]);
;                         if (hv == 0) { hw.x = r.x; hw.y = r.y; } else { hw.z = r.x; hw.w = r.y; } }
;                     *(u32x4*)(H + (size_t)(R0 + fr + 16 * m) * 2816 + col8) = hw;
;                     pv = cur; } }
	v_lshlrev_b32_e32 v114, 16, v101
	v_pk_fma_f32 v[62:63], v[92:93], v[120:121], v[62:63]
	v_and_b32_e32 v115, 0xffff0000, v101
	v_pk_mul_f32 v[70:71], v[62:63], s[30:31] op_sel_hi:[1,0]
	v_pk_mul_f32 v[62:63], v[62:63], 0.5 op_sel_hi:[1,0]
	v_med3_f32 v70, v70, s47, v225
	v_med3_f32 v71, v71, s47, v225
	v_pk_mul_f32 v[120:121], v[70:71], v[70:71]
	v_lshlrev_b32_e32 v68, 16, v69
	v_pk_fma_f32 v[130:131], v[120:121], s[34:35], v[118:119] op_sel_hi:[1,0,0] neg_lo:[1,0,0] neg_hi:[1,0,0]
	v_and_b32_e32 v69, 0xffff0000, v69
	v_pk_fma_f32 v[130:131], v[120:121], v[130:131], s[38:39] op_sel_hi:[1,1,0]
	v_mov_b32_dpp v1, v116 row_ror:1 row_mask:0xf bank_mask:0xf bound_ctrl:1
	v_pk_fma_f32 v[130:131], v[120:121], v[130:131], s[40:41] op_sel_hi:[1,1,0]
	v_pk_mul_f32 v[2:3], v[38:39], v[2:3]
	v_pk_fma_f32 v[130:131], v[120:121], v[130:131], s[42:43] op_sel_hi:[1,1,0]
	v_mov_b32_dpp v1, v112 row_shr:1 row_mask:0xf bank_mask:0xf
	v_pk_fma_f32 v[130:131], v[120:121], v[130:131], s[44:45] op_sel_hi:[1,1,0]
	v_readlane_b32 s64, v240, 23
	v_pk_fma_f32 v[130:131], v[120:121], v[130:131], s[46:47] op_sel_hi:[1,1,0]
	v_mov_b32_e32 v101, 0
	v_pk_fma_f32 v[120:121], v[120:121], v[130:131], s[48:49] op_sel_hi:[1,1,0]
	v_readlane_b32 s65, v240, 24
	v_pk_mul_f32 v[70:71], v[70:71], v[120:121]
	s_mov_b64 s[54:55], s[68:69]
	v_pk_fma_f32 v[62:63], v[62:63], v[70:71], v[62:63]
	v_pk_fma_f32 v[70:71], v[86:87], v[114:115], v[98:99]
	v_pk_mul_f32 v[56:57], v[56:57], v[62:63]
	v_lshlrev_b32_e32 v62, 16, v111
	v_and_b32_e32 v63, 0xffff0000, v111
	v_pk_fma_f32 v[68:69], v[90:91], v[68:69], v[70:71]
	v_cvt_pk_bf16_f32 v56, v56, v57
	s_nop 0
	v_pk_fma_f32 v[62:63], v[94:95], v[62:63], v[68:69]
	s_nop 0
	v_pk_mul_f32 v[68:69], v[62:63], s[30:31] op_sel_hi:[1,0]
	v_pk_mul_f32 v[62:63], v[62:63], 0.5 op_sel_hi:[1,0]
	v_med3_f32 v68, v68, s47, v225
	v_med3_f32 v69, v69, s47, v225
	v_pk_mul_f32 v[70:71], v[68:69], v[68:69]
	s_nop 0
	v_pk_fma_f32 v[114:115], v[70:71], s[34:35], v[118:119] op_sel_hi:[1,0,0] neg_lo:[1,0,0] neg_hi:[1,0,0]
	s_nop 0
	v_pk_fma_f32 v[114:115], v[70:71], v[114:115], s[38:39] op_sel_hi:[1,1,0]
	s_nop 0
	v_pk_fma_f32 v[114:115], v[70:71], v[114:115], s[40:41] op_sel_hi:[1,1,0]
	s_nop 0
	v_pk_fma_f32 v[114:115], v[70:71], v[114:115], s[42:43] op_sel_hi:[1,1,0]
	s_nop 0
	v_pk_fma_f32 v[114:115], v[70:71], v[114:115], s[44:45] op_sel_hi:[1,1,0]
	s_nop 0
	v_pk_fma_f32 v[114:115], v[70:71], v[114:115], s[46:47] op_sel_hi:[1,1,0]
	s_nop 0
	v_pk_fma_f32 v[70:71], v[70:71], v[114:115], s[48:49] op_sel_hi:[1,1,0]
	v_lshlrev_b32_e32 v114, 16, v112
	v_pk_mul_f32 v[68:69], v[68:69], v[70:71]
	v_and_b32_e32 v115, 0xffff0000, v112
	v_pk_fma_f32 v[62:63], v[62:63], v[68:69], v[62:63]
	v_mov_b32_dpp v69, v116 row_ror:2 row_mask:0xf bank_mask:0xf bound_ctrl:1
	v_pk_mul_f32 v[58:59], v[58:59], v[62:63]
	v_mov_b32_dpp v63, v117 row_ror:1 row_mask:0xf bank_mask:0xf bound_ctrl:1
	v_mov_b32_dpp v69, v112 row_shr:2 row_mask:0xf bank_mask:0xf
	v_lshlrev_b32_e32 v68, 16, v69
	v_and_b32_e32 v69, 0xffff0000, v69
	v_cvt_pk_bf16_f32 v57, v58, v59
	v_lshlrev_b32_e32 v58, 16, v1
	v_and_b32_e32 v59, 0xffff0000, v1
	v_pk_fma_f32 v[68:69], v[64:65], v[68:69], v[80:81]
	v_mov_b32_dpp v71, v117 row_ror:2 row_mask:0xf bank_mask:0xf bound_ctrl:1
	v_pk_fma_f32 v[58:59], v[72:73], v[58:59], v[68:69]
	v_mov_b32_dpp v63, v113 row_shr:1 row_mask:0xf bank_mask:0xf
	v_pk_fma_f32 v[58:59], v[76:77], v[114:115], v[58:59]
	v_mov_b32_dpp v71, v113 row_shr:2 row_mask:0xf bank_mask:0xf
	v_pk_mul_f32 v[68:69], v[58:59], s[30:31] op_sel_hi:[1,0]
	v_lshlrev_b32_e32 v70, 16, v71
	v_med3_f32 v68, v68, s47, v225
	v_med3_f32 v69, v69, s47, v225
	v_pk_mul_f32 v[114:115], v[68:69], v[68:69]
	v_and_b32_e32 v71, 0xffff0000, v71
	v_pk_fma_f32 v[116:117], v[114:115], s[34:35], v[118:119] op_sel_hi:[1,0,0] neg_lo:[1,0,0] neg_hi:[1,0,0]
	v_pk_mul_f32 v[58:59], v[58:59], 0.5 op_sel_hi:[1,0]
	v_pk_fma_f32 v[116:117], v[114:115], v[116:117], s[38:39] op_sel_hi:[1,1,0]
	v_lshlrev_b32_e32 v62, 16, v63
	v_pk_fma_f32 v[116:117], v[114:115], v[116:117], s[40:41] op_sel_hi:[1,1,0]
	v_and_b32_e32 v63, 0xffff0000, v63
	v_pk_fma_f32 v[116:117], v[114:115], v[116:117], s[42:43] op_sel_hi:[1,1,0]
	v_mov_b32_dpp v1, v110 row_ror:1 row_mask:0xf bank_mask:0xf bound_ctrl:1
	v_pk_fma_f32 v[116:117], v[114:115], v[116:117], s[44:45] op_sel_hi:[1,1,0]
	s_nop 0
	v_pk_fma_f32 v[116:117], v[114:115], v[116:117], s[46:47] op_sel_hi:[1,1,0]
	v_mov_b32_dpp v1, v106 row_shr:1 row_mask:0xf bank_mask:0xf
	v_pk_fma_f32 v[114:115], v[114:115], v[116:117], s[48:49] op_sel_hi:[1,1,0]
	s_nop 0
	v_pk_mul_f32 v[68:69], v[68:69], v[114:115]
	s_nop 0
	v_pk_fma_f32 v[58:59], v[58:59], v[68:69], v[58:59]
	v_pk_fma_f32 v[68:69], v[66:67], v[70:71], v[82:83]
	v_pk_mul_f32 v[52:53], v[52:53], v[58:59]
	v_lshlrev_b32_e32 v58, 16, v113
	v_and_b32_e32 v59, 0xffff0000, v113
	v_pk_fma_f32 v[62:63], v[74:75], v[62:63], v[68:69]
	s_nop 0
	v_pk_fma_f32 v[58:59], v[78:79], v[58:59], v[62:63]
	s_nop 0
	v_pk_mul_f32 v[62:63], v[58:59], s[30:31] op_sel_hi:[1,0]
	v_pk_mul_f32 v[58:59], v[58:59], 0.5 op_sel_hi:[1,0]
	v_med3_f32 v62, v62, s47, v225
	v_med3_f32 v63, v63, s47, v225
	v_pk_mul_f32 v[68:69], v[62:63], v[62:63]
	s_nop 0
	v_pk_fma_f32 v[70:71], v[68:69], s[34:35], v[118:119] op_sel_hi:[1,0,0] neg_lo:[1,0,0] neg_hi:[1,0,0]
	s_nop 0
	v_pk_fma_f32 v[70:71], v[68:69], v[70:71], s[38:39] op_sel_hi:[1,1,0]
	s_nop 0
	v_pk_fma_f32 v[70:71], v[68:69], v[70:71], s[40:41] op_sel_hi:[1,1,0]
	s_nop 0
	v_pk_fma_f32 v[70:71], v[68:69], v[70:71], s[42:43] op_sel_hi:[1,1,0]
	s_nop 0
	v_pk_fma_f32 v[70:71], v[68:69], v[70:71], s[44:45] op_sel_hi:[1,1,0]
	s_nop 0
; __device__ __forceinline__ unsigned cvt_pk_bf16(float lo, float hi) { unsigned r; asm volatile("v_cvt_pk_bf16_f32 %0, %1, %2" : "=v"(r) : "v"(lo), "v"(hi)); return r; }
;     static __device__ __forceinline__ u32x2 finish2(const float (&g0)[4], const float (&g1)[4], const float (&g2)[4], const float (&w0)[4], const float (&w1)[4], const float (&w2)[4], const float (&bb)[4],
;                                                     const f32x4 v, float rs) {
;         float h[4];
; #pragma unroll
;         for (int j = 0; j < 4; j += 2) {
;             const f32x2 gc = (f32x2){bb[j] + w0[j] * g2[j] + w1[j] * g1[j] + w2[j] * g0[j], bb[j + 1] + w0[j + 1] * g2[j + 1] + w1[j + 1] * g1[j + 1] + w2[j + 1] * g0[j + 1]};
;             const f32x2 ge = gelu_pk(gc) * ((f32x2){v[j], v[j + 1]} * rs); h[j] = ge.x; h[j + 1] = ge.y; }
;         u32x2 w; w.x = cvt_pk_bf16(h[0], h[1]); w.y = cvt_pk_bf16(h[2], h[3]); return w;
;     }
;     __device__ __forceinline__ void operator()(const f32x4 (&acc)[2][2][4][2], const Unit& u, int wr, int wc, int fr, int fq) const {
;     ...
;             for (int ai = 0; ai < 2; ++ai) { const int R0 = u.rb + ai * HALF + wr * 64; const bf16_t* gp = G + (size_t)(R0 + fr) * 2816 + col8;
;                 u32x4 gq[4], prv = (u32x4){0u, 0u, 0u, 0u};
; #pragma unroll
;                 for (int m = 0; m < 4; ++m) gq[m] = *(const u32x4*)(gp + (size_t)m * 16 * 2816);
;                 if ((R0 & 8191) != 0) prv = *(const u32x4*)(gp - (size_t)16 * 2816);
;                 u32x4 pv = prv;
; #pragma unroll
;                 for (int m = 0; m < 4; ++m) { const u32x4 cur = gq[m]; u32x4 hw;
; #pragma unroll
;                     for (int hv = 0; hv < 2; ++hv) { const u32x2 c2 = half2(cur, hv), p2 = half2(pv, hv);
;                         const u32x2 q1 = dpp_prev<1>(p2, c2), q2 = dpp_prev<2>(p2, c2);
;                         float g0[4], g1[4], g2[4]; unpk4(c2, g0); unpk4(q1, g1); unpk4(q2, g2);
;                         const u32x2 r = finish2(g0, g1, g2, w0[hv], w1[hv], w2[hv], bb[hv], acc[ai][bj][m][hv], rs8[ai][m]);
;                         if (hv == 0) { hw.x = r.x; hw.y = r.y; } else { hw.z = r.x; hw.w = r.y; } }
;                     *(u32x4*)(H + (size_t)(R0 + fr + 16 * m) * 2816 + col8) = hw;
;                     pv = cur; } }
	v_pk_fma_f32 v[70:71], v[68:69], v[70:71], s[46:47] op_sel_hi:[1,1,0]
	s_nop 0
	v_pk_fma_f32 v[68:69], v[68:69], v[70:71], s[48:49] op_sel_hi:[1,1,0]
	s_nop 0
	v_pk_mul_f32 v[62:63], v[62:63], v[68:69]
	s_nop 0
	v_pk_fma_f32 v[58:59], v[58:59], v[62:63], v[58:59]
	v_lshlrev_b32_e32 v62, 16, v106
	v_pk_mul_f32 v[54:55], v[54:55], v[58:59]
	v_cvt_pk_bf16_f32 v58, v52, v53
	v_lshl_add_u64 v[52:53], v[176:177], 0, v[60:61]
	v_cvt_pk_bf16_f32 v59, v54, v55
	global_store_dwordx4 v[52:53], v[56:59], off sc1
	v_lshlrev_b32_e32 v52, 16, v1
	v_and_b32_e32 v53, 0xffff0000, v1
	v_mov_b32_dpp v57, v110 row_ror:2 row_mask:0xf bank_mask:0xf bound_ctrl:1
	v_and_b32_e32 v63, 0xffff0000, v106
	v_mov_b32_dpp v59, v111 row_ror:2 row_mask:0xf bank_mask:0xf bound_ctrl:1
	v_mov_b32_dpp v57, v106 row_shr:2 row_mask:0xf bank_mask:0xf
	v_lshlrev_b32_e32 v56, 16, v57
	v_and_b32_e32 v57, 0xffff0000, v57
	v_pk_fma_f32 v[56:57], v[84:85], v[56:57], v[96:97]
	v_mov_b32_dpp v55, v111 row_ror:1 row_mask:0xf bank_mask:0xf bound_ctrl:1
	v_pk_fma_f32 v[52:53], v[88:89], v[52:53], v[56:57]
	v_mov_b32_dpp v59, v107 row_shr:2 row_mask:0xf bank_mask:0xf
	v_pk_fma_f32 v[52:53], v[92:93], v[62:63], v[52:53]
	v_mov_b32_dpp v55, v107 row_shr:1 row_mask:0xf bank_mask:0xf
	v_pk_mul_f32 v[56:57], v[52:53], s[30:31] op_sel_hi:[1,0]
	v_lshlrev_b32_e32 v58, 16, v59
	v_med3_f32 v56, v56, s47, v225
	v_med3_f32 v57, v57, s47, v225
	v_pk_mul_f32 v[62:63], v[56:57], v[56:57]
	v_and_b32_e32 v59, 0xffff0000, v59
	v_pk_fma_f32 v[68:69], v[62:63], s[34:35], v[118:119] op_sel_hi:[1,0,0] neg_lo:[1,0,0] neg_hi:[1,0,0]
	v_pk_mul_f32 v[52:53], v[52:53], 0.5 op_sel_hi:[1,0]
	v_pk_fma_f32 v[68:69], v[62:63], v[68:69], s[38:39] op_sel_hi:[1,1,0]
	v_lshlrev_b32_e32 v54, 16, v55
	v_pk_fma_f32 v[68:69], v[62:63], v[68:69], s[40:41] op_sel_hi:[1,1,0]
	v_and_b32_e32 v55, 0xffff0000, v55
	v_pk_fma_f32 v[68:69], v[62:63], v[68:69], s[42:43] op_sel_hi:[1,1,0]
	v_mov_b32_dpp v1, v112 row_ror:1 row_mask:0xf bank_mask:0xf bound_ctrl:1
	v_pk_fma_f32 v[68:69], v[62:63], v[68:69], s[44:45] op_sel_hi:[1,1,0]
	s_nop 0
	v_pk_fma_f32 v[68:69], v[62:63], v[68:69], s[46:47] op_sel_hi:[1,1,0]
	v_mov_b32_dpp v1, v108 row_shr:1 row_mask:0xf bank_mask:0xf
	v_pk_fma_f32 v[62:63], v[62:63], v[68:69], s[48:49] op_sel_hi:[1,1,0]
	s_nop 0
	v_pk_mul_f32 v[56:57], v[56:57], v[62:63]
	s_nop 0
	v_pk_fma_f32 v[52:53], v[52:53], v[56:57], v[52:53]
	v_pk_fma_f32 v[56:57], v[86:87], v[58:59], v[98:99]
	v_pk_mul_f32 v[48:49], v[48:49], v[52:53]
	v_lshlrev_b32_e32 v52, 16, v107
	v_and_b32_e32 v53, 0xffff0000, v107
	v_pk_fma_f32 v[54:55], v[90:91], v[54:55], v[56:57]
	v_cvt_pk_bf16_f32 v48, v48, v49
	s_nop 0
	v_pk_fma_f32 v[52:53], v[94:95], v[52:53], v[54:55]
	s_nop 0
	v_pk_mul_f32 v[54:55], v[52:53], s[30:31] op_sel_hi:[1,0]
	v_pk_mul_f32 v[52:53], v[52:53], 0.5 op_sel_hi:[1,0]
	v_med3_f32 v54, v54, s47, v225
	v_med3_f32 v55, v55, s47, v225
	v_pk_mul_f32 v[56:57], v[54:55], v[54:55]
	s_nop 0
	v_pk_fma_f32 v[58:59], v[56:57], s[34:35], v[118:119] op_sel_hi:[1,0,0] neg_lo:[1,0,0] neg_hi:[1,0,0]
	s_nop 0
	v_pk_fma_f32 v[58:59], v[56:57], v[58:59], s[38:39] op_sel_hi:[1,1,0]
	s_nop 0
	v_pk_fma_f32 v[58:59], v[56:57], v[58:59], s[40:41] op_sel_hi:[1,1,0]
	s_nop 0
	v_pk_fma_f32 v[58:59], v[56:57], v[58:59], s[42:43] op_sel_hi:[1,1,0]
	s_nop 0
	v_pk_fma_f32 v[58:59], v[56:57], v[58:59], s[44:45] op_sel_hi:[1,1,0]
	s_nop 0
	v_pk_fma_f32 v[58:59], v[56:57], v[58:59], s[46:47] op_sel_hi:[1,1,0]
	s_nop 0
	v_pk_fma_f32 v[56:57], v[56:57], v[58:59], s[48:49] op_sel_hi:[1,1,0]
	v_lshlrev_b32_e32 v58, 16, v108
	v_pk_mul_f32 v[54:55], v[54:55], v[56:57]
	v_and_b32_e32 v59, 0xffff0000, v108
	v_pk_fma_f32 v[52:53], v[52:53], v[54:55], v[52:53]
	v_mov_b32_dpp v55, v112 row_ror:2 row_mask:0xf bank_mask:0xf bound_ctrl:1
	v_pk_mul_f32 v[50:51], v[50:51], v[52:53]
	v_mov_b32_dpp v57, v113 row_ror:2 row_mask:0xf bank_mask:0xf bound_ctrl:1
	v_mov_b32_dpp v55, v108 row_shr:2 row_mask:0xf bank_mask:0xf
	v_lshlrev_b32_e32 v54, 16, v55
	v_and_b32_e32 v55, 0xffff0000, v55
	v_cvt_pk_bf16_f32 v49, v50, v51
	v_lshlrev_b32_e32 v50, 16, v1
	v_and_b32_e32 v51, 0xffff0000, v1
	v_pk_fma_f32 v[54:55], v[64:65], v[54:55], v[80:81]
	v_mov_b32_dpp v53, v113 row_ror:1 row_mask:0xf bank_mask:0xf bound_ctrl:1
	v_pk_fma_f32 v[50:51], v[72:73], v[50:51], v[54:55]
	v_mov_b32_dpp v57, v109 row_shr:2 row_mask:0xf bank_mask:0xf
	v_pk_fma_f32 v[50:51], v[76:77], v[58:59], v[50:51]
	v_mov_b32_dpp v53, v109 row_shr:1 row_mask:0xf bank_mask:0xf
	v_pk_mul_f32 v[54:55], v[50:51], s[30:31] op_sel_hi:[1,0]
	v_lshlrev_b32_e32 v56, 16, v57
	v_med3_f32 v54, v54, s47, v225
	v_med3_f32 v55, v55, s47, v225
	v_pk_mul_f32 v[58:59], v[54:55], v[54:55]
	v_and_b32_e32 v57, 0xffff0000, v57
	v_pk_fma_f32 v[62:63], v[58:59], s[34:35], v[118:119] op_sel_hi:[1,0,0] neg_lo:[1,0,0] neg_hi:[1,0,0]
	v_pk_mul_f32 v[50:51], v[50:51], 0.5 op_sel_hi:[1,0]
	v_pk_fma_f32 v[62:63], v[58:59], v[62:63], s[38:39] op_sel_hi:[1,1,0]
	v_lshlrev_b32_e32 v52, 16, v53
	v_pk_fma_f32 v[62:63], v[58:59], v[62:63], s[40:41] op_sel_hi:[1,1,0]
	v_and_b32_e32 v53, 0xffff0000, v53
	v_pk_fma_f32 v[62:63], v[58:59], v[62:63], s[42:43] op_sel_hi:[1,1,0]
	v_mov_b32_dpp v1, v106 row_ror:1 row_mask:0xf bank_mask:0xf bound_ctrl:1
	v_pk_fma_f32 v[62:63], v[58:59], v[62:63], s[44:45] op_sel_hi:[1,1,0]
	s_nop 0
	v_pk_fma_f32 v[62:63], v[58:59], v[62:63], s[46:47] op_sel_hi:[1,1,0]
	v_mov_b32_dpp v1, v102 row_shr:1 row_mask:0xf bank_mask:0xf
	v_pk_fma_f32 v[58:59], v[58:59], v[62:63], s[48:49] op_sel_hi:[1,1,0]
	s_nop 0
	v_pk_mul_f32 v[54:55], v[54:55], v[58:59]
	s_nop 0
	v_pk_fma_f32 v[50:51], v[50:51], v[54:55], v[50:51]
; __device__ __forceinline__ unsigned cvt_pk_bf16(float lo, float hi) { unsigned r; asm volatile("v_cvt_pk_bf16_f32 %0, %1, %2" : "=v"(r) : "v"(lo), "v"(hi)); return r; }
;     static __device__ __forceinline__ u32x2 finish2(const float (&g0)[4], const float (&g1)[4], const float (&g2)[4], const float (&w0)[4], const float (&w1)[4], const float (&w2)[4], const float (&bb)[4],
;                                                     const f32x4 v, float rs) {
;         float h[4];
; #pragma unroll
;         for (int j = 0; j < 4; j += 2) {
;             const f32x2 gc = (f32x2){bb[j] + w0[j] * g2[j] + w1[j] * g1[j] + w2[j] * g0[j], bb[j + 1] + w0[j + 1] * g2[j + 1] + w1[j + 1] * g1[j + 1] + w2[j + 1] * g0[j + 1]};
;             const f32x2 ge = gelu_pk(gc) * ((f32x2){v[j], v[j + 1]} * rs); h[j] = ge.x; h[j + 1] = ge.y; }
;         u32x2 w; w.x = cvt_pk_bf16(h[0], h[1]); w.y = cvt_pk_bf16(h[2], h[3]); return w;
;     }
;     __device__ __forceinline__ void operator()(const f32x4 (&acc)[2][2][4][2], const Unit& u, int wr, int wc, int fr, int fq) const {
;     ...
;             for (int ai = 0; ai < 2; ++ai) { const int R0 = u.rb + ai * HALF + wr * 64; const bf16_t* gp = G + (size_t)(R0 + fr) * 2816 + col8;
;                 u32x4 gq[4], prv = (u32x4){0u, 0u, 0u, 0u};
; #pragma unroll
;                 for (int m = 0; m < 4; ++m) gq[m] = *(const u32x4*)(gp + (size_t)m * 16 * 2816);
;                 if ((R0 & 8191) != 0) prv = *(const u32x4*)(gp - (size_t)16 * 2816);
;                 u32x4 pv = prv;
; #pragma unroll
;                 for (int m = 0; m < 4; ++m) { const u32x4 cur = gq[m]; u32x4 hw;
; #pragma unroll
;                     for (int hv = 0; hv < 2; ++hv) { const u32x2 c2 = half2(cur, hv), p2 = half2(pv, hv);
;                         const u32x2 q1 = dpp_prev<1>(p2, c2), q2 = dpp_prev<2>(p2, c2);
;                         float g0[4], g1[4], g2[4]; unpk4(c2, g0); unpk4(q1, g1); unpk4(q2, g2);
;                         const u32x2 r = finish2(g0, g1, g2, w0[hv], w1[hv], w2[hv], bb[hv], acc[ai][bj][m][hv], rs8[ai][m]);
;                         if (hv == 0) { hw.x = r.x; hw.y = r.y; } else { hw.z = r.x; hw.w = r.y; } }
;                     *(u32x4*)(H + (size_t)(R0 + fr + 16 * m) * 2816 + col8) = hw;
;                     pv = cur; } }
	v_pk_fma_f32 v[54:55], v[66:67], v[56:57], v[82:83]
	v_pk_mul_f32 v[44:45], v[44:45], v[50:51]
	v_lshlrev_b32_e32 v50, 16, v109
	v_and_b32_e32 v51, 0xffff0000, v109
	v_pk_fma_f32 v[52:53], v[74:75], v[52:53], v[54:55]
	s_nop 0
	v_pk_fma_f32 v[50:51], v[78:79], v[50:51], v[52:53]
	s_nop 0
	v_pk_mul_f32 v[52:53], v[50:51], s[30:31] op_sel_hi:[1,0]
	v_pk_mul_f32 v[50:51], v[50:51], 0.5 op_sel_hi:[1,0]
	v_med3_f32 v52, v52, s47, v225
	v_med3_f32 v53, v53, s47, v225
	v_pk_mul_f32 v[54:55], v[52:53], v[52:53]
	s_nop 0
	v_pk_fma_f32 v[56:57], v[54:55], s[34:35], v[118:119] op_sel_hi:[1,0,0] neg_lo:[1,0,0] neg_hi:[1,0,0]
	s_nop 0
	v_pk_fma_f32 v[56:57], v[54:55], v[56:57], s[38:39] op_sel_hi:[1,1,0]
	s_nop 0
	v_pk_fma_f32 v[56:57], v[54:55], v[56:57], s[40:41] op_sel_hi:[1,1,0]
	s_nop 0
	v_pk_fma_f32 v[56:57], v[54:55], v[56:57], s[42:43] op_sel_hi:[1,1,0]
	s_nop 0
	v_pk_fma_f32 v[56:57], v[54:55], v[56:57], s[44:45] op_sel_hi:[1,1,0]
	s_nop 0
	v_pk_fma_f32 v[56:57], v[54:55], v[56:57], s[46:47] op_sel_hi:[1,1,0]
	s_nop 0
	v_pk_fma_f32 v[54:55], v[54:55], v[56:57], s[48:49] op_sel_hi:[1,1,0]
	v_lshl_add_u64 v[56:57], v[166:167], 0, v[60:61]
	v_pk_mul_f32 v[52:53], v[52:53], v[54:55]
	s_nop 0
	v_pk_fma_f32 v[50:51], v[50:51], v[52:53], v[50:51]
	v_lshlrev_b32_e32 v52, 16, v102
	v_pk_mul_f32 v[46:47], v[46:47], v[50:51]
	v_cvt_pk_bf16_f32 v50, v44, v45
	v_lshl_add_u64 v[44:45], v[172:173], 0, v[60:61]
	v_cvt_pk_bf16_f32 v51, v46, v47
	global_store_dwordx4 v[44:45], v[48:51], off sc1
	v_lshlrev_b32_e32 v44, 16, v1
	v_and_b32_e32 v45, 0xffff0000, v1
	v_mov_b32_dpp v49, v106 row_ror:2 row_mask:0xf bank_mask:0xf bound_ctrl:1
	v_and_b32_e32 v53, 0xffff0000, v102
	v_mov_b32_dpp v51, v107 row_ror:2 row_mask:0xf bank_mask:0xf bound_ctrl:1
	v_mov_b32_dpp v49, v102 row_shr:2 row_mask:0xf bank_mask:0xf
	v_lshlrev_b32_e32 v48, 16, v49
	v_and_b32_e32 v49, 0xffff0000, v49
	v_pk_fma_f32 v[48:49], v[84:85], v[48:49], v[96:97]
	v_mov_b32_dpp v47, v107 row_ror:1 row_mask:0xf bank_mask:0xf bound_ctrl:1
	v_pk_fma_f32 v[44:45], v[88:89], v[44:45], v[48:49]
	v_mov_b32_dpp v51, v103 row_shr:2 row_mask:0xf bank_mask:0xf
	v_pk_fma_f32 v[44:45], v[92:93], v[52:53], v[44:45]
	v_mov_b32_dpp v47, v103 row_shr:1 row_mask:0xf bank_mask:0xf
	v_pk_mul_f32 v[48:49], v[44:45], s[30:31] op_sel_hi:[1,0]
	v_lshlrev_b32_e32 v50, 16, v51
	v_med3_f32 v48, v48, s47, v225
	v_med3_f32 v49, v49, s47, v225
	v_pk_mul_f32 v[52:53], v[48:49], v[48:49]
	v_and_b32_e32 v51, 0xffff0000, v51
	v_pk_fma_f32 v[54:55], v[52:53], s[34:35], v[118:119] op_sel_hi:[1,0,0] neg_lo:[1,0,0] neg_hi:[1,0,0]
	v_pk_mul_f32 v[44:45], v[44:45], 0.5 op_sel_hi:[1,0]
	v_pk_fma_f32 v[54:55], v[52:53], v[54:55], s[38:39] op_sel_hi:[1,1,0]
	v_lshlrev_b32_e32 v46, 16, v47
	v_pk_fma_f32 v[54:55], v[52:53], v[54:55], s[40:41] op_sel_hi:[1,1,0]
	v_and_b32_e32 v47, 0xffff0000, v47
	v_pk_fma_f32 v[54:55], v[52:53], v[54:55], s[42:43] op_sel_hi:[1,1,0]
	v_mov_b32_dpp v1, v108 row_ror:1 row_mask:0xf bank_mask:0xf bound_ctrl:1
	v_pk_fma_f32 v[54:55], v[52:53], v[54:55], s[44:45] op_sel_hi:[1,1,0]
	v_mov_b32_e32 v102, 0
	v_pk_fma_f32 v[54:55], v[52:53], v[54:55], s[46:47] op_sel_hi:[1,1,0]
	v_mov_b32_dpp v1, v104 row_shr:1 row_mask:0xf bank_mask:0xf
	v_pk_fma_f32 v[52:53], v[52:53], v[54:55], s[48:49] op_sel_hi:[1,1,0]
	s_nop 0
	v_pk_mul_f32 v[48:49], v[48:49], v[52:53]
	s_nop 0
	v_pk_fma_f32 v[44:45], v[44:45], v[48:49], v[44:45]
	v_pk_fma_f32 v[48:49], v[86:87], v[50:51], v[98:99]
	v_pk_mul_f32 v[40:41], v[40:41], v[44:45]
	v_lshlrev_b32_e32 v44, 16, v103
	v_and_b32_e32 v45, 0xffff0000, v103
	v_pk_fma_f32 v[46:47], v[90:91], v[46:47], v[48:49]
	v_cvt_pk_bf16_f32 v52, v40, v41
	v_lshlrev_b32_e32 v40, 16, v1
	v_pk_fma_f32 v[44:45], v[94:95], v[44:45], v[46:47]
	v_and_b32_e32 v41, 0xffff0000, v1
	v_pk_mul_f32 v[46:47], v[44:45], s[30:31] op_sel_hi:[1,0]
	v_pk_mul_f32 v[44:45], v[44:45], 0.5 op_sel_hi:[1,0]
	v_med3_f32 v46, v46, s47, v225
	v_med3_f32 v47, v47, s47, v225
	v_pk_mul_f32 v[48:49], v[46:47], v[46:47]
	v_mov_b32_e32 v103, 0
	v_pk_fma_f32 v[50:51], v[48:49], s[34:35], v[118:119] op_sel_hi:[1,0,0] neg_lo:[1,0,0] neg_hi:[1,0,0]
	s_nop 0
	v_pk_fma_f32 v[50:51], v[48:49], v[50:51], s[38:39] op_sel_hi:[1,1,0]
	s_nop 0
	v_pk_fma_f32 v[50:51], v[48:49], v[50:51], s[40:41] op_sel_hi:[1,1,0]
	s_nop 0
	v_pk_fma_f32 v[50:51], v[48:49], v[50:51], s[42:43] op_sel_hi:[1,1,0]
	s_nop 0
	v_pk_fma_f32 v[50:51], v[48:49], v[50:51], s[44:45] op_sel_hi:[1,1,0]
	s_nop 0
	v_pk_fma_f32 v[50:51], v[48:49], v[50:51], s[46:47] op_sel_hi:[1,1,0]
	s_nop 0
	v_pk_fma_f32 v[48:49], v[48:49], v[50:51], s[48:49] op_sel_hi:[1,1,0]
	s_nop 0
	v_pk_mul_f32 v[46:47], v[46:47], v[48:49]
	v_lshlrev_b32_e32 v48, 16, v104
	v_pk_fma_f32 v[44:45], v[44:45], v[46:47], v[44:45]
	v_and_b32_e32 v49, 0xffff0000, v104
	v_pk_mul_f32 v[42:43], v[42:43], v[44:45]
	v_mov_b32_dpp v45, v108 row_ror:2 row_mask:0xf bank_mask:0xf bound_ctrl:1
	v_mov_b32_dpp v47, v109 row_ror:2 row_mask:0xf bank_mask:0xf bound_ctrl:1
	v_cvt_pk_bf16_f32 v53, v42, v43
	v_mov_b32_dpp v43, v109 row_ror:1 row_mask:0xf bank_mask:0xf bound_ctrl:1
	v_mov_b32_dpp v45, v104 row_shr:2 row_mask:0xf bank_mask:0xf
	v_lshlrev_b32_e32 v44, 16, v45
	v_and_b32_e32 v45, 0xffff0000, v45
	v_pk_fma_f32 v[44:45], v[64:65], v[44:45], v[80:81]
	v_mov_b32_dpp v47, v105 row_shr:2 row_mask:0xf bank_mask:0xf
	v_pk_fma_f32 v[40:41], v[72:73], v[40:41], v[44:45]
	v_mov_b32_dpp v43, v105 row_shr:1 row_mask:0xf bank_mask:0xf
	v_pk_fma_f32 v[40:41], v[76:77], v[48:49], v[40:41]
	v_lshlrev_b32_e32 v46, 16, v47
	v_pk_mul_f32 v[44:45], v[40:41], s[30:31] op_sel_hi:[1,0]
	v_and_b32_e32 v47, 0xffff0000, v47
	v_med3_f32 v44, v44, s47, v225
; __device__ __forceinline__ unsigned cvt_pk_bf16(float lo, float hi) { unsigned r; asm volatile("v_cvt_pk_bf16_f32 %0, %1, %2" : "=v"(r) : "v"(lo), "v"(hi)); return r; }
;     static __device__ __forceinline__ u32x2 finish2(const float (&g0)[4], const float (&g1)[4], const float (&g2)[4], const float (&w0)[4], const float (&w1)[4], const float (&w2)[4], const float (&bb)[4],
;                                                     const f32x4 v, float rs) {
;         float h[4];
; #pragma unroll
;         for (int j = 0; j < 4; j += 2) {
;             const f32x2 gc = (f32x2){bb[j] + w0[j] * g2[j] + w1[j] * g1[j] + w2[j] * g0[j], bb[j + 1] + w0[j + 1] * g2[j + 1] + w1[j + 1] * g1[j + 1] + w2[j + 1] * g0[j + 1]};
;             const f32x2 ge = gelu_pk(gc) * ((f32x2){v[j], v[j + 1]} * rs); h[j] = ge.x; h[j + 1] = ge.y; }
;         u32x2 w; w.x = cvt_pk_bf16(h[0], h[1]); w.y = cvt_pk_bf16(h[2], h[3]); return w;
;     }
;     __device__ __forceinline__ void operator()(const f32x4 (&acc)[2][2][4][2], const Unit& u, int wr, int wc, int fr, int fq) const {
;     ...
;             for (int ai = 0; ai < 2; ++ai) { const int R0 = u.rb + ai * HALF + wr * 64; const bf16_t* gp = G + (size_t)(R0 + fr) * 2816 + col8;
;                 u32x4 gq[4], prv = (u32x4){0u, 0u, 0u, 0u};
; #pragma unroll
;                 for (int m = 0; m < 4; ++m) gq[m] = *(const u32x4*)(gp + (size_t)m * 16 * 2816);
;                 if ((R0 & 8191) != 0) prv = *(const u32x4*)(gp - (size_t)16 * 2816);
;                 u32x4 pv = prv;
; #pragma unroll
;                 for (int m = 0; m < 4; ++m) { const u32x4 cur = gq[m]; u32x4 hw;
; #pragma unroll
;                     for (int hv = 0; hv < 2; ++hv) { const u32x2 c2 = half2(cur, hv), p2 = half2(pv, hv);
;                         const u32x2 q1 = dpp_prev<1>(p2, c2), q2 = dpp_prev<2>(p2, c2);
;                         float g0[4], g1[4], g2[4]; unpk4(c2, g0); unpk4(q1, g1); unpk4(q2, g2);
;                         const u32x2 r = finish2(g0, g1, g2, w0[hv], w1[hv], w2[hv], bb[hv], acc[ai][bj][m][hv], rs8[ai][m]);
;                         if (hv == 0) { hw.x = r.x; hw.y = r.y; } else { hw.z = r.x; hw.w = r.y; } }
;                     *(u32x4*)(H + (size_t)(R0 + fr + 16 * m) * 2816 + col8) = hw;
;                     pv = cur; } }
	v_med3_f32 v45, v45, s47, v225
	v_pk_mul_f32 v[48:49], v[44:45], v[44:45]
	v_pk_mul_f32 v[40:41], v[40:41], 0.5 op_sel_hi:[1,0]
	v_pk_fma_f32 v[50:51], v[48:49], s[34:35], v[118:119] op_sel_hi:[1,0,0] neg_lo:[1,0,0] neg_hi:[1,0,0]
	v_lshlrev_b32_e32 v42, 16, v43
	v_pk_fma_f32 v[50:51], v[48:49], v[50:51], s[38:39] op_sel_hi:[1,1,0]
	v_and_b32_e32 v43, 0xffff0000, v43
	v_pk_fma_f32 v[50:51], v[48:49], v[50:51], s[40:41] op_sel_hi:[1,1,0]
	s_nop 0
	v_pk_fma_f32 v[50:51], v[48:49], v[50:51], s[42:43] op_sel_hi:[1,1,0]
	s_nop 0
	v_pk_fma_f32 v[50:51], v[48:49], v[50:51], s[44:45] op_sel_hi:[1,1,0]
	s_nop 0
	v_pk_fma_f32 v[50:51], v[48:49], v[50:51], s[46:47] op_sel_hi:[1,1,0]
	s_nop 0
	v_pk_fma_f32 v[48:49], v[48:49], v[50:51], s[48:49] op_sel_hi:[1,1,0]
	s_nop 0
	v_pk_mul_f32 v[44:45], v[44:45], v[48:49]
	s_nop 0
	v_pk_fma_f32 v[40:41], v[40:41], v[44:45], v[40:41]
	v_pk_fma_f32 v[44:45], v[66:67], v[46:47], v[82:83]
	v_pk_mul_f32 v[36:37], v[36:37], v[40:41]
	v_lshlrev_b32_e32 v40, 16, v105
	v_and_b32_e32 v41, 0xffff0000, v105
	v_pk_fma_f32 v[42:43], v[74:75], v[42:43], v[44:45]
	v_cvt_pk_bf16_f32 v54, v36, v37
	s_nop 0
	v_pk_fma_f32 v[40:41], v[78:79], v[40:41], v[42:43]
	s_nop 0
	v_pk_mul_f32 v[42:43], v[40:41], s[30:31] op_sel_hi:[1,0]
	v_pk_mul_f32 v[40:41], v[40:41], 0.5 op_sel_hi:[1,0]
	v_med3_f32 v42, v42, s47, v225
	v_med3_f32 v43, v43, s47, v225
	v_pk_mul_f32 v[44:45], v[42:43], v[42:43]
	s_nop 0
	v_pk_fma_f32 v[46:47], v[44:45], s[34:35], v[118:119] op_sel_hi:[1,0,0] neg_lo:[1,0,0] neg_hi:[1,0,0]
	s_nop 0
	v_pk_fma_f32 v[46:47], v[44:45], v[46:47], s[38:39] op_sel_hi:[1,1,0]
	s_nop 0
	v_pk_fma_f32 v[46:47], v[44:45], v[46:47], s[40:41] op_sel_hi:[1,1,0]
	s_nop 0
	v_pk_fma_f32 v[46:47], v[44:45], v[46:47], s[42:43] op_sel_hi:[1,1,0]
	s_nop 0
	v_pk_fma_f32 v[46:47], v[44:45], v[46:47], s[44:45] op_sel_hi:[1,1,0]
	s_nop 0
	v_pk_fma_f32 v[46:47], v[44:45], v[46:47], s[46:47] op_sel_hi:[1,1,0]
	s_nop 0
	v_pk_fma_f32 v[44:45], v[44:45], v[46:47], s[48:49] op_sel_hi:[1,1,0]
	s_nop 0
	v_pk_mul_f32 v[42:43], v[42:43], v[44:45]
	s_nop 0
	v_pk_fma_f32 v[40:41], v[40:41], v[42:43], v[40:41]
	s_nop 0
	v_pk_mul_f32 v[2:3], v[2:3], v[40:41]
	s_nop 0
	v_cvt_pk_bf16_f32 v55, v2, v3
	v_lshl_add_u64 v[2:3], v[164:165], 0, v[60:61]
	v_add_co_u32_e32 v36, vcc, s10, v2
	s_nop 1
	v_addc_co_u32_e32 v37, vcc, 0, v3, vcc
	global_load_dwordx4 v[48:51], v[2:3], off
	global_load_dwordx4 v[44:47], v[36:37], off
	v_add_co_u32_e32 v36, vcc, 0x2c000, v2
	s_nop 1
	v_addc_co_u32_e32 v37, vcc, 0, v3, vcc
	v_add_co_u32_e32 v38, vcc, 0x42000, v2
	s_nop 1
	v_addc_co_u32_e32 v39, vcc, 0, v3, vcc
	global_load_dwordx4 v[40:43], v[36:37], off
	s_nop 0
	global_load_dwordx4 v[36:39], v[38:39], off
	s_andn2_b64 vcc, exec, s[2:3]
	global_store_dwordx4 v[56:57], v[52:55], off sc1
	s_cbranch_vccnz .LBB0_1020
	v_add_co_u32_e32 v2, vcc, 0xfffea000, v2
	s_nop 1
	v_addc_co_u32_e32 v3, vcc, -1, v3, vcc
	global_load_dwordx4 v[100:103], v[2:3], off
.LBB0_1020:
	s_waitcnt vmcnt(0)
	s_nop 0
	v_mov_b32_dpp v55, v100 row_ror:2 row_mask:0xf bank_mask:0xf bound_ctrl:1
	v_mov_b32_dpp v1, v100 row_ror:1 row_mask:0xf bank_mask:0xf bound_ctrl:1
	v_lshlrev_b32_e32 v58, 16, v48
	v_mov_b32_dpp v55, v48 row_shr:2 row_mask:0xf bank_mask:0xf
	v_mov_b32_dpp v1, v48 row_shr:1 row_mask:0xf bank_mask:0xf
	v_lshlrev_b32_e32 v54, 16, v55
	v_and_b32_e32 v55, 0xffff0000, v55
	v_lshlrev_b32_e32 v2, 16, v1
	v_and_b32_e32 v3, 0xffff0000, v1
	v_pk_fma_f32 v[54:55], v[84:85], v[54:55], v[96:97]
	v_and_b32_e32 v59, 0xffff0000, v48
	v_pk_fma_f32 v[2:3], v[88:89], v[2:3], v[54:55]
	v_mov_b32_dpp v57, v101 row_ror:2 row_mask:0xf bank_mask:0xf bound_ctrl:1
	v_pk_fma_f32 v[54:55], v[92:93], v[58:59], v[2:3]
	v_mov_b32_dpp v53, v101 row_ror:1 row_mask:0xf bank_mask:0xf bound_ctrl:1
	v_pk_mul_f32 v[2:3], v[54:55], s[30:31] op_sel_hi:[1,0]
	v_mov_b32_dpp v57, v49 row_shr:2 row_mask:0xf bank_mask:0xf
	v_med3_f32 v58, v2, s47, v225
	v_med3_f32 v59, v3, s47, v225
	v_pk_mul_f32 v[62:63], v[58:59], v[58:59]
	v_mov_b64_e32 v[2:3], s[36:37]
	v_pk_fma_f32 v[68:69], v[62:63], s[34:35], v[2:3] op_sel_hi:[1,0,0] neg_lo:[1,0,0] neg_hi:[1,0,0]
	v_mov_b32_e32 v129, v128
	v_pk_fma_f32 v[68:69], v[62:63], v[68:69], s[38:39] op_sel_hi:[1,1,0]
	v_mov_b32_dpp v53, v49 row_shr:1 row_mask:0xf bank_mask:0xf
	v_pk_fma_f32 v[68:69], v[62:63], v[68:69], s[40:41] op_sel_hi:[1,1,0]
	v_lshlrev_b32_e32 v56, 16, v57
	v_pk_fma_f32 v[68:69], v[62:63], v[68:69], s[42:43] op_sel_hi:[1,1,0]
	v_and_b32_e32 v57, 0xffff0000, v57
	v_pk_fma_f32 v[68:69], v[62:63], v[68:69], s[44:45] op_sel_hi:[1,1,0]
	v_pk_mul_f32 v[54:55], v[54:55], 0.5 op_sel_hi:[1,0]
	v_pk_fma_f32 v[68:69], v[62:63], v[68:69], s[46:47] op_sel_hi:[1,1,0]
	v_lshlrev_b32_e32 v52, 16, v53
	v_pk_fma_f32 v[62:63], v[62:63], v[68:69], s[48:49] op_sel_hi:[1,1,0]
	v_and_b32_e32 v53, 0xffff0000, v53
	v_pk_mul_f32 v[58:59], v[58:59], v[62:63]
	v_pk_mul_f32 v[32:33], v[32:33], v[128:129]
	v_pk_fma_f32 v[54:55], v[54:55], v[58:59], v[54:55]
	v_pk_fma_f32 v[56:57], v[86:87], v[56:57], v[98:99]
	v_pk_mul_f32 v[32:33], v[32:33], v[54:55]
	v_lshlrev_b32_e32 v54, 16, v49
	v_and_b32_e32 v55, 0xffff0000, v49
	v_pk_fma_f32 v[52:53], v[90:91], v[52:53], v[56:57]
	v_pk_mul_f32 v[34:35], v[34:35], v[128:129]
	v_pk_fma_f32 v[52:53], v[94:95], v[54:55], v[52:53]
	v_mov_b32_dpp v1, v102 row_ror:1 row_mask:0xf bank_mask:0xf bound_ctrl:1
	v_pk_mul_f32 v[54:55], v[52:53], s[30:31] op_sel_hi:[1,0]
	v_pk_mul_f32 v[52:53], v[52:53], 0.5 op_sel_hi:[1,0]
	v_med3_f32 v54, v54, s47, v225
	v_med3_f32 v55, v55, s47, v225
	v_pk_mul_f32 v[56:57], v[54:55], v[54:55]
	v_mov_b32_dpp v1, v50 row_shr:1 row_mask:0xf bank_mask:0xf
; __device__ __forceinline__ unsigned cvt_pk_bf16(float lo, float hi) { unsigned r; asm volatile("v_cvt_pk_bf16_f32 %0, %1, %2" : "=v"(r) : "v"(lo), "v"(hi)); return r; }
;     static __device__ __forceinline__ u32x2 finish2(const float (&g0)[4], const float (&g1)[4], const float (&g2)[4], const float (&w0)[4], const float (&w1)[4], const float (&w2)[4], const float (&bb)[4],
;                                                     const f32x4 v, float rs) {
;         float h[4];
; #pragma unroll
;         for (int j = 0; j < 4; j += 2) {
;             const f32x2 gc = (f32x2){bb[j] + w0[j] * g2[j] + w1[j] * g1[j] + w2[j] * g0[j], bb[j + 1] + w0[j + 1] * g2[j + 1] + w1[j + 1] * g1[j + 1] + w2[j + 1] * g0[j + 1]};
;             const f32x2 ge = gelu_pk(gc) * ((f32x2){v[j], v[j + 1]} * rs); h[j] = ge.x; h[j + 1] = ge.y; }
;         u32x2 w; w.x = cvt_pk_bf16(h[0], h[1]); w.y = cvt_pk_bf16(h[2], h[3]); return w;
;     }
;     __device__ __forceinline__ void operator()(const f32x4 (&acc)[2][2][4][2], const Unit& u, int wr, int wc, int fr, int fq) const {
;     ...
;             for (int ai = 0; ai < 2; ++ai) { const int R0 = u.rb + ai * HALF + wr * 64; const bf16_t* gp = G + (size_t)(R0 + fr) * 2816 + col8;
;                 u32x4 gq[4], prv = (u32x4){0u, 0u, 0u, 0u};
; #pragma unroll
;                 for (int m = 0; m < 4; ++m) gq[m] = *(const u32x4*)(gp + (size_t)m * 16 * 2816);
;                 if ((R0 & 8191) != 0) prv = *(const u32x4*)(gp - (size_t)16 * 2816);
;                 u32x4 pv = prv;
; #pragma unroll
;                 for (int m = 0; m < 4; ++m) { const u32x4 cur = gq[m]; u32x4 hw;
; #pragma unroll
;                     for (int hv = 0; hv < 2; ++hv) { const u32x2 c2 = half2(cur, hv), p2 = half2(pv, hv);
;                         const u32x2 q1 = dpp_prev<1>(p2, c2), q2 = dpp_prev<2>(p2, c2);
;                         float g0[4], g1[4], g2[4]; unpk4(c2, g0); unpk4(q1, g1); unpk4(q2, g2);
;                         const u32x2 r = finish2(g0, g1, g2, w0[hv], w1[hv], w2[hv], bb[hv], acc[ai][bj][m][hv], rs8[ai][m]);
;                         if (hv == 0) { hw.x = r.x; hw.y = r.y; } else { hw.z = r.x; hw.w = r.y; } }
;                     *(u32x4*)(H + (size_t)(R0 + fr + 16 * m) * 2816 + col8) = hw;
;                     pv = cur; } }
	v_pk_fma_f32 v[58:59], v[56:57], s[34:35], v[2:3] op_sel_hi:[1,0,0] neg_lo:[1,0,0] neg_hi:[1,0,0]
	v_cvt_pk_bf16_f32 v32, v32, v33
	v_pk_mul_f32 v[28:29], v[28:29], v[128:129]
	v_pk_fma_f32 v[58:59], v[56:57], v[58:59], s[38:39] op_sel_hi:[1,1,0]
	v_pk_mul_f32 v[30:31], v[30:31], v[128:129]
	v_pk_fma_f32 v[58:59], v[56:57], v[58:59], s[40:41] op_sel_hi:[1,1,0]
	v_mov_b32_e32 v127, v126
	v_pk_fma_f32 v[58:59], v[56:57], v[58:59], s[42:43] op_sel_hi:[1,1,0]
	v_pk_mul_f32 v[24:25], v[24:25], v[126:127]
	v_pk_fma_f32 v[58:59], v[56:57], v[58:59], s[44:45] op_sel_hi:[1,1,0]
	v_pk_mul_f32 v[26:27], v[26:27], v[126:127]
	v_pk_fma_f32 v[58:59], v[56:57], v[58:59], s[46:47] op_sel_hi:[1,1,0]
	v_pk_mul_f32 v[20:21], v[20:21], v[126:127]
	v_pk_fma_f32 v[56:57], v[56:57], v[58:59], s[48:49] op_sel_hi:[1,1,0]
	v_lshlrev_b32_e32 v58, 16, v50
	v_pk_mul_f32 v[54:55], v[54:55], v[56:57]
	v_and_b32_e32 v59, 0xffff0000, v50
	v_pk_fma_f32 v[52:53], v[52:53], v[54:55], v[52:53]
	v_mov_b32_dpp v55, v102 row_ror:2 row_mask:0xf bank_mask:0xf bound_ctrl:1
	v_pk_mul_f32 v[34:35], v[34:35], v[52:53]
	v_mov_b32_dpp v57, v103 row_ror:2 row_mask:0xf bank_mask:0xf bound_ctrl:1
	v_mov_b32_dpp v55, v50 row_shr:2 row_mask:0xf bank_mask:0xf
	v_lshlrev_b32_e32 v54, 16, v55
	v_and_b32_e32 v55, 0xffff0000, v55
	v_cvt_pk_bf16_f32 v33, v34, v35
	v_lshlrev_b32_e32 v34, 16, v1
	v_and_b32_e32 v35, 0xffff0000, v1
	v_pk_fma_f32 v[54:55], v[64:65], v[54:55], v[80:81]
	v_mov_b32_dpp v53, v103 row_ror:1 row_mask:0xf bank_mask:0xf bound_ctrl:1
	v_pk_fma_f32 v[34:35], v[72:73], v[34:35], v[54:55]
	v_mov_b32_dpp v57, v51 row_shr:2 row_mask:0xf bank_mask:0xf
	v_pk_fma_f32 v[34:35], v[76:77], v[58:59], v[34:35]
	v_mov_b32_dpp v53, v51 row_shr:1 row_mask:0xf bank_mask:0xf
	v_pk_mul_f32 v[54:55], v[34:35], s[30:31] op_sel_hi:[1,0]
	v_lshlrev_b32_e32 v56, 16, v57
	v_med3_f32 v54, v54, s47, v225
	v_med3_f32 v55, v55, s47, v225
	v_pk_mul_f32 v[58:59], v[54:55], v[54:55]
	v_and_b32_e32 v57, 0xffff0000, v57
	v_pk_fma_f32 v[62:63], v[58:59], s[34:35], v[2:3] op_sel_hi:[1,0,0] neg_lo:[1,0,0] neg_hi:[1,0,0]
	v_pk_mul_f32 v[34:35], v[34:35], 0.5 op_sel_hi:[1,0]
	v_pk_fma_f32 v[62:63], v[58:59], v[62:63], s[38:39] op_sel_hi:[1,1,0]
	v_lshlrev_b32_e32 v52, 16, v53
	v_pk_fma_f32 v[62:63], v[58:59], v[62:63], s[40:41] op_sel_hi:[1,1,0]
	v_and_b32_e32 v53, 0xffff0000, v53
	v_pk_fma_f32 v[62:63], v[58:59], v[62:63], s[42:43] op_sel_hi:[1,1,0]
	v_mov_b32_dpp v1, v48 row_ror:1 row_mask:0xf bank_mask:0xf bound_ctrl:1
	v_pk_fma_f32 v[62:63], v[58:59], v[62:63], s[44:45] op_sel_hi:[1,1,0]
	v_pk_mul_f32 v[22:23], v[22:23], v[126:127]
	v_pk_fma_f32 v[62:63], v[58:59], v[62:63], s[46:47] op_sel_hi:[1,1,0]
	v_mov_b32_dpp v1, v44 row_shr:1 row_mask:0xf bank_mask:0xf
	v_pk_fma_f32 v[58:59], v[58:59], v[62:63], s[48:49] op_sel_hi:[1,1,0]
	v_mov_b32_e32 v125, v124
	v_pk_mul_f32 v[54:55], v[54:55], v[58:59]
	v_pk_mul_f32 v[16:17], v[16:17], v[124:125]
	v_pk_fma_f32 v[34:35], v[34:35], v[54:55], v[34:35]
	v_pk_fma_f32 v[54:55], v[66:67], v[56:57], v[82:83]
	v_pk_mul_f32 v[28:29], v[28:29], v[34:35]
	v_lshlrev_b32_e32 v34, 16, v51
	v_and_b32_e32 v35, 0xffff0000, v51
	v_pk_fma_f32 v[52:53], v[74:75], v[52:53], v[54:55]
	v_pk_mul_f32 v[18:19], v[18:19], v[124:125]
	v_pk_fma_f32 v[34:35], v[78:79], v[34:35], v[52:53]
	v_pk_mul_f32 v[12:13], v[12:13], v[124:125]
	v_pk_mul_f32 v[52:53], v[34:35], s[30:31] op_sel_hi:[1,0]
	v_pk_mul_f32 v[34:35], v[34:35], 0.5 op_sel_hi:[1,0]
	v_med3_f32 v52, v52, s47, v225
	v_med3_f32 v53, v53, s47, v225
	v_pk_mul_f32 v[54:55], v[52:53], v[52:53]
	v_pk_mul_f32 v[14:15], v[14:15], v[124:125]
	v_pk_fma_f32 v[56:57], v[54:55], s[34:35], v[2:3] op_sel_hi:[1,0,0] neg_lo:[1,0,0] neg_hi:[1,0,0]
	v_mov_b32_e32 v123, v122
	v_pk_fma_f32 v[56:57], v[54:55], v[56:57], s[38:39] op_sel_hi:[1,1,0]
	v_pk_mul_f32 v[8:9], v[8:9], v[122:123]
	v_pk_fma_f32 v[56:57], v[54:55], v[56:57], s[40:41] op_sel_hi:[1,1,0]
	v_pk_mul_f32 v[10:11], v[10:11], v[122:123]
	v_pk_fma_f32 v[56:57], v[54:55], v[56:57], s[42:43] op_sel_hi:[1,1,0]
	v_pk_mul_f32 v[4:5], v[4:5], v[122:123]
	v_pk_fma_f32 v[56:57], v[54:55], v[56:57], s[44:45] op_sel_hi:[1,1,0]
	v_pk_mul_f32 v[6:7], v[6:7], v[122:123]
	v_pk_fma_f32 v[56:57], v[54:55], v[56:57], s[46:47] op_sel_hi:[1,1,0]
	s_nop 0
	v_pk_fma_f32 v[54:55], v[54:55], v[56:57], s[48:49] op_sel_hi:[1,1,0]
	s_nop 0
	v_pk_mul_f32 v[52:53], v[52:53], v[54:55]
	s_nop 0
	v_pk_fma_f32 v[34:35], v[34:35], v[52:53], v[34:35]
	s_nop 0
	v_pk_mul_f32 v[30:31], v[30:31], v[34:35]
	v_cvt_pk_bf16_f32 v34, v28, v29
	v_lshl_add_u64 v[28:29], v[168:169], 0, v[60:61]
	v_cvt_pk_bf16_f32 v35, v30, v31
	global_store_dwordx4 v[28:29], v[32:35], off sc1
	v_lshlrev_b32_e32 v28, 16, v1
	v_and_b32_e32 v29, 0xffff0000, v1
	v_mov_b32_dpp v33, v48 row_ror:2 row_mask:0xf bank_mask:0xf bound_ctrl:1
	v_mov_b32_dpp v31, v49 row_ror:1 row_mask:0xf bank_mask:0xf bound_ctrl:1
	v_mov_b32_dpp v35, v49 row_ror:2 row_mask:0xf bank_mask:0xf bound_ctrl:1
	v_mov_b32_dpp v33, v44 row_shr:2 row_mask:0xf bank_mask:0xf
	v_lshlrev_b32_e32 v32, 16, v33
	v_and_b32_e32 v33, 0xffff0000, v33
	v_pk_fma_f32 v[32:33], v[84:85], v[32:33], v[96:97]
	v_lshlrev_b32_e32 v48, 16, v44
	v_and_b32_e32 v49, 0xffff0000, v44
	v_pk_fma_f32 v[28:29], v[88:89], v[28:29], v[32:33]
	v_mov_b32_dpp v35, v45 row_shr:2 row_mask:0xf bank_mask:0xf
	v_pk_fma_f32 v[28:29], v[92:93], v[48:49], v[28:29]
	v_mov_b32_dpp v31, v45 row_shr:1 row_mask:0xf bank_mask:0xf
	v_pk_mul_f32 v[32:33], v[28:29], s[30:31] op_sel_hi:[1,0]
	v_lshlrev_b32_e32 v34, 16, v35
	v_med3_f32 v32, v32, s47, v225
	v_med3_f32 v33, v33, s47, v225
	v_pk_mul_f32 v[48:49], v[32:33], v[32:33]
; __device__ __forceinline__ unsigned cvt_pk_bf16(float lo, float hi) { unsigned r; asm volatile("v_cvt_pk_bf16_f32 %0, %1, %2" : "=v"(r) : "v"(lo), "v"(hi)); return r; }
;     static __device__ __forceinline__ u32x2 finish2(const float (&g0)[4], const float (&g1)[4], const float (&g2)[4], const float (&w0)[4], const float (&w1)[4], const float (&w2)[4], const float (&bb)[4],
;                                                     const f32x4 v, float rs) {
;         float h[4];
; #pragma unroll
;         for (int j = 0; j < 4; j += 2) {
;             const f32x2 gc = (f32x2){bb[j] + w0[j] * g2[j] + w1[j] * g1[j] + w2[j] * g0[j], bb[j + 1] + w0[j + 1] * g2[j + 1] + w1[j + 1] * g1[j + 1] + w2[j + 1] * g0[j + 1]};
;             const f32x2 ge = gelu_pk(gc) * ((f32x2){v[j], v[j + 1]} * rs); h[j] = ge.x; h[j + 1] = ge.y; }
;         u32x2 w; w.x = cvt_pk_bf16(h[0], h[1]); w.y = cvt_pk_bf16(h[2], h[3]); return w;
;     }
;     __device__ __forceinline__ void operator()(const f32x4 (&acc)[2][2][4][2], const Unit& u, int wr, int wc, int fr, int fq) const {
;     ...
;             for (int ai = 0; ai < 2; ++ai) { const int R0 = u.rb + ai * HALF + wr * 64; const bf16_t* gp = G + (size_t)(R0 + fr) * 2816 + col8;
;                 u32x4 gq[4], prv = (u32x4){0u, 0u, 0u, 0u};
; #pragma unroll
;                 for (int m = 0; m < 4; ++m) gq[m] = *(const u32x4*)(gp + (size_t)m * 16 * 2816);
;                 if ((R0 & 8191) != 0) prv = *(const u32x4*)(gp - (size_t)16 * 2816);
;                 u32x4 pv = prv;
; #pragma unroll
;                 for (int m = 0; m < 4; ++m) { const u32x4 cur = gq[m]; u32x4 hw;
; #pragma unroll
;                     for (int hv = 0; hv < 2; ++hv) { const u32x2 c2 = half2(cur, hv), p2 = half2(pv, hv);
;                         const u32x2 q1 = dpp_prev<1>(p2, c2), q2 = dpp_prev<2>(p2, c2);
;                         float g0[4], g1[4], g2[4]; unpk4(c2, g0); unpk4(q1, g1); unpk4(q2, g2);
;                         const u32x2 r = finish2(g0, g1, g2, w0[hv], w1[hv], w2[hv], bb[hv], acc[ai][bj][m][hv], rs8[ai][m]);
;                         if (hv == 0) { hw.x = r.x; hw.y = r.y; } else { hw.z = r.x; hw.w = r.y; } }
;                     *(u32x4*)(H + (size_t)(R0 + fr + 16 * m) * 2816 + col8) = hw;
;                     pv = cur; } }
	v_and_b32_e32 v35, 0xffff0000, v35
	v_pk_fma_f32 v[52:53], v[48:49], s[34:35], v[2:3] op_sel_hi:[1,0,0] neg_lo:[1,0,0] neg_hi:[1,0,0]
	v_pk_mul_f32 v[28:29], v[28:29], 0.5 op_sel_hi:[1,0]
	v_pk_fma_f32 v[52:53], v[48:49], v[52:53], s[38:39] op_sel_hi:[1,1,0]
	v_lshlrev_b32_e32 v30, 16, v31
	v_pk_fma_f32 v[52:53], v[48:49], v[52:53], s[40:41] op_sel_hi:[1,1,0]
	v_and_b32_e32 v31, 0xffff0000, v31
	v_pk_fma_f32 v[52:53], v[48:49], v[52:53], s[42:43] op_sel_hi:[1,1,0]
	v_mov_b32_dpp v1, v50 row_ror:1 row_mask:0xf bank_mask:0xf bound_ctrl:1
	v_pk_fma_f32 v[52:53], v[48:49], v[52:53], s[44:45] op_sel_hi:[1,1,0]
	s_nop 0
	v_pk_fma_f32 v[52:53], v[48:49], v[52:53], s[46:47] op_sel_hi:[1,1,0]
	v_mov_b32_dpp v1, v46 row_shr:1 row_mask:0xf bank_mask:0xf
	v_pk_fma_f32 v[48:49], v[48:49], v[52:53], s[48:49] op_sel_hi:[1,1,0]
	s_nop 0
	v_pk_mul_f32 v[32:33], v[32:33], v[48:49]
	s_nop 0
	v_pk_fma_f32 v[28:29], v[28:29], v[32:33], v[28:29]
	v_pk_fma_f32 v[32:33], v[86:87], v[34:35], v[98:99]
	v_pk_mul_f32 v[24:25], v[24:25], v[28:29]
	v_lshlrev_b32_e32 v28, 16, v45
	v_and_b32_e32 v29, 0xffff0000, v45
	v_pk_fma_f32 v[30:31], v[90:91], v[30:31], v[32:33]
	v_cvt_pk_bf16_f32 v24, v24, v25
	s_nop 0
	v_pk_fma_f32 v[28:29], v[94:95], v[28:29], v[30:31]
	s_nop 0
	v_pk_mul_f32 v[30:31], v[28:29], s[30:31] op_sel_hi:[1,0]
	v_pk_mul_f32 v[28:29], v[28:29], 0.5 op_sel_hi:[1,0]
	v_med3_f32 v30, v30, s47, v225
	v_med3_f32 v31, v31, s47, v225
	v_pk_mul_f32 v[32:33], v[30:31], v[30:31]
	s_nop 0
	v_pk_fma_f32 v[34:35], v[32:33], s[34:35], v[2:3] op_sel_hi:[1,0,0] neg_lo:[1,0,0] neg_hi:[1,0,0]
	s_nop 0
	v_pk_fma_f32 v[34:35], v[32:33], v[34:35], s[38:39] op_sel_hi:[1,1,0]
	s_nop 0
	v_pk_fma_f32 v[34:35], v[32:33], v[34:35], s[40:41] op_sel_hi:[1,1,0]
	s_nop 0
	v_pk_fma_f32 v[34:35], v[32:33], v[34:35], s[42:43] op_sel_hi:[1,1,0]
	s_nop 0
	v_pk_fma_f32 v[34:35], v[32:33], v[34:35], s[44:45] op_sel_hi:[1,1,0]
	s_nop 0
	v_pk_fma_f32 v[34:35], v[32:33], v[34:35], s[46:47] op_sel_hi:[1,1,0]
	s_nop 0
	v_pk_fma_f32 v[32:33], v[32:33], v[34:35], s[48:49] op_sel_hi:[1,1,0]
	v_lshlrev_b32_e32 v34, 16, v46
	v_pk_mul_f32 v[30:31], v[30:31], v[32:33]
	v_and_b32_e32 v35, 0xffff0000, v46
	v_pk_fma_f32 v[28:29], v[28:29], v[30:31], v[28:29]
	v_mov_b32_dpp v31, v50 row_ror:2 row_mask:0xf bank_mask:0xf bound_ctrl:1
	v_pk_mul_f32 v[26:27], v[26:27], v[28:29]
	v_mov_b32_dpp v33, v51 row_ror:2 row_mask:0xf bank_mask:0xf bound_ctrl:1
	v_mov_b32_dpp v31, v46 row_shr:2 row_mask:0xf bank_mask:0xf
	v_lshlrev_b32_e32 v30, 16, v31
	v_and_b32_e32 v31, 0xffff0000, v31
	v_cvt_pk_bf16_f32 v25, v26, v27
	v_lshlrev_b32_e32 v26, 16, v1
	v_and_b32_e32 v27, 0xffff0000, v1
	v_pk_fma_f32 v[30:31], v[64:65], v[30:31], v[80:81]
	v_mov_b32_dpp v29, v51 row_ror:1 row_mask:0xf bank_mask:0xf bound_ctrl:1
	v_pk_fma_f32 v[26:27], v[72:73], v[26:27], v[30:31]
	v_mov_b32_dpp v33, v47 row_shr:2 row_mask:0xf bank_mask:0xf
	v_pk_fma_f32 v[26:27], v[76:77], v[34:35], v[26:27]
	v_mov_b32_dpp v29, v47 row_shr:1 row_mask:0xf bank_mask:0xf
	v_pk_mul_f32 v[30:31], v[26:27], s[30:31] op_sel_hi:[1,0]
	v_lshlrev_b32_e32 v32, 16, v33
	v_med3_f32 v30, v30, s47, v225
	v_med3_f32 v31, v31, s47, v225
	v_pk_mul_f32 v[34:35], v[30:31], v[30:31]
	v_and_b32_e32 v33, 0xffff0000, v33
	v_pk_fma_f32 v[48:49], v[34:35], s[34:35], v[2:3] op_sel_hi:[1,0,0] neg_lo:[1,0,0] neg_hi:[1,0,0]
	v_pk_mul_f32 v[26:27], v[26:27], 0.5 op_sel_hi:[1,0]
	v_pk_fma_f32 v[48:49], v[34:35], v[48:49], s[38:39] op_sel_hi:[1,1,0]
	v_lshlrev_b32_e32 v28, 16, v29
	v_pk_fma_f32 v[48:49], v[34:35], v[48:49], s[40:41] op_sel_hi:[1,1,0]
	v_and_b32_e32 v29, 0xffff0000, v29
	v_pk_fma_f32 v[48:49], v[34:35], v[48:49], s[42:43] op_sel_hi:[1,1,0]
	v_mov_b32_dpp v1, v44 row_ror:1 row_mask:0xf bank_mask:0xf bound_ctrl:1
	v_pk_fma_f32 v[48:49], v[34:35], v[48:49], s[44:45] op_sel_hi:[1,1,0]
	s_nop 0
	v_pk_fma_f32 v[48:49], v[34:35], v[48:49], s[46:47] op_sel_hi:[1,1,0]
	v_mov_b32_dpp v1, v40 row_shr:1 row_mask:0xf bank_mask:0xf
	v_pk_fma_f32 v[34:35], v[34:35], v[48:49], s[48:49] op_sel_hi:[1,1,0]
	s_nop 0
	v_pk_mul_f32 v[30:31], v[30:31], v[34:35]
	s_nop 0
	v_pk_fma_f32 v[26:27], v[26:27], v[30:31], v[26:27]
	v_pk_fma_f32 v[30:31], v[66:67], v[32:33], v[82:83]
	v_pk_mul_f32 v[20:21], v[20:21], v[26:27]
	v_lshlrev_b32_e32 v26, 16, v47
	v_and_b32_e32 v27, 0xffff0000, v47
	v_pk_fma_f32 v[28:29], v[74:75], v[28:29], v[30:31]
	s_nop 0
	v_pk_fma_f32 v[26:27], v[78:79], v[26:27], v[28:29]
	s_nop 0
	v_pk_mul_f32 v[28:29], v[26:27], s[30:31] op_sel_hi:[1,0]
	v_pk_mul_f32 v[26:27], v[26:27], 0.5 op_sel_hi:[1,0]
	v_med3_f32 v28, v28, s47, v225
	v_med3_f32 v29, v29, s47, v225
	v_pk_mul_f32 v[30:31], v[28:29], v[28:29]
	s_nop 0
	v_pk_fma_f32 v[32:33], v[30:31], s[34:35], v[2:3] op_sel_hi:[1,0,0] neg_lo:[1,0,0] neg_hi:[1,0,0]
	s_nop 0
	v_pk_fma_f32 v[32:33], v[30:31], v[32:33], s[38:39] op_sel_hi:[1,1,0]
	s_nop 0
	v_pk_fma_f32 v[32:33], v[30:31], v[32:33], s[40:41] op_sel_hi:[1,1,0]
	s_nop 0
	v_pk_fma_f32 v[32:33], v[30:31], v[32:33], s[42:43] op_sel_hi:[1,1,0]
	s_nop 0
	v_pk_fma_f32 v[32:33], v[30:31], v[32:33], s[44:45] op_sel_hi:[1,1,0]
	s_nop 0
	v_pk_fma_f32 v[32:33], v[30:31], v[32:33], s[46:47] op_sel_hi:[1,1,0]
	s_nop 0
	v_pk_fma_f32 v[30:31], v[30:31], v[32:33], s[48:49] op_sel_hi:[1,1,0]
	s_nop 0
	v_pk_mul_f32 v[28:29], v[28:29], v[30:31]
	s_nop 0
	v_pk_fma_f32 v[26:27], v[26:27], v[28:29], v[26:27]
	v_lshlrev_b32_e32 v28, 16, v40
	v_pk_mul_f32 v[22:23], v[22:23], v[26:27]
	v_cvt_pk_bf16_f32 v26, v20, v21
	v_lshl_add_u64 v[20:21], v[170:171], 0, v[60:61]
	v_cvt_pk_bf16_f32 v27, v22, v23
	global_store_dwordx4 v[20:21], v[24:27], off sc1
	v_lshlrev_b32_e32 v20, 16, v1
; __device__ __forceinline__ unsigned cvt_pk_bf16(float lo, float hi) { unsigned r; asm volatile("v_cvt_pk_bf16_f32 %0, %1, %2" : "=v"(r) : "v"(lo), "v"(hi)); return r; }
; __device__ __forceinline__ f32x2 gelu_pk(f32x2 v) {
;     f32x2 x = v * 0.70710678118f;
;     x.x = __builtin_amdgcn_fmed3f(x.x, -2.9f, 2.9f); x.y = __builtin_amdgcn_fmed3f(x.y, -2.9f, 2.9f);
;     const f32x2 t = x * x;
;     f32x2 p = t * (-4.953124630e-07f) + 1.987094038e-05f;
;     p = p * t + (-3.472001117e-04f); p = p * t + 3.517547622e-03f; p = p * t + (-2.333305031e-02f); p = p * t + 1.087993085e-01f; p = p * t + (-3.740358949e-01f); p = p * t + 1.128076553e+00f;
;     const f32x2 hv = v * 0.5f;
;     return hv * (x * p) + hv;
; }
;     static __device__ __forceinline__ u32x2 finish2(const float (&g0)[4], const float (&g1)[4], const float (&g2)[4], const float (&w0)[4], const float (&w1)[4], const float (&w2)[4], const float (&bb)[4],
;                                                     const f32x4 v, float rs) {
;         float h[4];
; #pragma unroll
;         for (int j = 0; j < 4; j += 2) {
;             const f32x2 gc = (f32x2){bb[j] + w0[j] * g2[j] + w1[j] * g1[j] + w2[j] * g0[j], bb[j + 1] + w0[j + 1] * g2[j + 1] + w1[j + 1] * g1[j + 1] + w2[j + 1] * g0[j + 1]};
;             const f32x2 ge = gelu_pk(gc) * ((f32x2){v[j], v[j + 1]} * rs); h[j] = ge.x; h[j + 1] = ge.y; }
;         u32x2 w; w.x = cvt_pk_bf16(h[0], h[1]); w.y = cvt_pk_bf16(h[2], h[3]); return w;
;     }
	v_and_b32_e32 v21, 0xffff0000, v1
	v_mov_b32_dpp v25, v44 row_ror:2 row_mask:0xf bank_mask:0xf bound_ctrl:1
	v_and_b32_e32 v29, 0xffff0000, v40
	v_mov_b32_dpp v27, v45 row_ror:2 row_mask:0xf bank_mask:0xf bound_ctrl:1
	v_mov_b32_dpp v25, v40 row_shr:2 row_mask:0xf bank_mask:0xf
	v_lshlrev_b32_e32 v24, 16, v25
	v_and_b32_e32 v25, 0xffff0000, v25
	v_pk_fma_f32 v[24:25], v[84:85], v[24:25], v[96:97]
	v_mov_b32_dpp v23, v45 row_ror:1 row_mask:0xf bank_mask:0xf bound_ctrl:1
	v_pk_fma_f32 v[20:21], v[88:89], v[20:21], v[24:25]
	v_mov_b32_dpp v27, v41 row_shr:2 row_mask:0xf bank_mask:0xf
	v_pk_fma_f32 v[20:21], v[92:93], v[28:29], v[20:21]
	v_mov_b32_dpp v23, v41 row_shr:1 row_mask:0xf bank_mask:0xf
	v_pk_mul_f32 v[24:25], v[20:21], s[30:31] op_sel_hi:[1,0]
	v_lshlrev_b32_e32 v26, 16, v27
	v_med3_f32 v24, v24, s47, v225
	v_med3_f32 v25, v25, s47, v225
	v_pk_mul_f32 v[28:29], v[24:25], v[24:25]
	v_and_b32_e32 v27, 0xffff0000, v27
	v_pk_fma_f32 v[30:31], v[28:29], s[34:35], v[2:3] op_sel_hi:[1,0,0] neg_lo:[1,0,0] neg_hi:[1,0,0]
	v_pk_mul_f32 v[20:21], v[20:21], 0.5 op_sel_hi:[1,0]
	v_pk_fma_f32 v[30:31], v[28:29], v[30:31], s[38:39] op_sel_hi:[1,1,0]
	v_lshlrev_b32_e32 v22, 16, v23
	v_pk_fma_f32 v[30:31], v[28:29], v[30:31], s[40:41] op_sel_hi:[1,1,0]
	v_and_b32_e32 v23, 0xffff0000, v23
	v_pk_fma_f32 v[30:31], v[28:29], v[30:31], s[42:43] op_sel_hi:[1,1,0]
	v_mov_b32_dpp v1, v46 row_ror:1 row_mask:0xf bank_mask:0xf bound_ctrl:1
	v_pk_fma_f32 v[30:31], v[28:29], v[30:31], s[44:45] op_sel_hi:[1,1,0]
	s_nop 0
	v_pk_fma_f32 v[30:31], v[28:29], v[30:31], s[46:47] op_sel_hi:[1,1,0]
	v_mov_b32_dpp v1, v42 row_shr:1 row_mask:0xf bank_mask:0xf
	v_pk_fma_f32 v[28:29], v[28:29], v[30:31], s[48:49] op_sel_hi:[1,1,0]
	s_nop 0
	v_pk_mul_f32 v[24:25], v[24:25], v[28:29]
	s_nop 0
	v_pk_fma_f32 v[20:21], v[20:21], v[24:25], v[20:21]
	v_pk_fma_f32 v[24:25], v[86:87], v[26:27], v[98:99]
	v_pk_mul_f32 v[16:17], v[16:17], v[20:21]
	v_lshlrev_b32_e32 v20, 16, v41
	v_and_b32_e32 v21, 0xffff0000, v41
	v_pk_fma_f32 v[22:23], v[90:91], v[22:23], v[24:25]
	v_cvt_pk_bf16_f32 v16, v16, v17
	s_nop 0
	v_pk_fma_f32 v[20:21], v[94:95], v[20:21], v[22:23]
	s_nop 0
	v_pk_mul_f32 v[22:23], v[20:21], s[30:31] op_sel_hi:[1,0]
	v_pk_mul_f32 v[20:21], v[20:21], 0.5 op_sel_hi:[1,0]
	v_med3_f32 v22, v22, s47, v225
	v_med3_f32 v23, v23, s47, v225
	v_pk_mul_f32 v[24:25], v[22:23], v[22:23]
	s_nop 0
	v_pk_fma_f32 v[26:27], v[24:25], s[34:35], v[2:3] op_sel_hi:[1,0,0] neg_lo:[1,0,0] neg_hi:[1,0,0]
	s_nop 0
	v_pk_fma_f32 v[26:27], v[24:25], v[26:27], s[38:39] op_sel_hi:[1,1,0]
	s_nop 0
	v_pk_fma_f32 v[26:27], v[24:25], v[26:27], s[40:41] op_sel_hi:[1,1,0]
	s_nop 0
	v_pk_fma_f32 v[26:27], v[24:25], v[26:27], s[42:43] op_sel_hi:[1,1,0]
	s_nop 0
	v_pk_fma_f32 v[26:27], v[24:25], v[26:27], s[44:45] op_sel_hi:[1,1,0]
	s_nop 0
	v_pk_fma_f32 v[26:27], v[24:25], v[26:27], s[46:47] op_sel_hi:[1,1,0]
	s_nop 0
	v_pk_fma_f32 v[24:25], v[24:25], v[26:27], s[48:49] op_sel_hi:[1,1,0]
	v_lshlrev_b32_e32 v26, 16, v42
	v_pk_mul_f32 v[22:23], v[22:23], v[24:25]
	v_and_b32_e32 v27, 0xffff0000, v42
	v_pk_fma_f32 v[20:21], v[20:21], v[22:23], v[20:21]
	v_mov_b32_dpp v23, v46 row_ror:2 row_mask:0xf bank_mask:0xf bound_ctrl:1
	v_pk_mul_f32 v[18:19], v[18:19], v[20:21]
	v_mov_b32_dpp v25, v47 row_ror:2 row_mask:0xf bank_mask:0xf bound_ctrl:1
	v_mov_b32_dpp v23, v42 row_shr:2 row_mask:0xf bank_mask:0xf
	v_lshlrev_b32_e32 v22, 16, v23
	v_and_b32_e32 v23, 0xffff0000, v23
	v_cvt_pk_bf16_f32 v17, v18, v19
	v_lshlrev_b32_e32 v18, 16, v1
	v_and_b32_e32 v19, 0xffff0000, v1
	v_pk_fma_f32 v[22:23], v[64:65], v[22:23], v[80:81]
	v_mov_b32_dpp v21, v47 row_ror:1 row_mask:0xf bank_mask:0xf bound_ctrl:1
	v_pk_fma_f32 v[18:19], v[72:73], v[18:19], v[22:23]
	v_mov_b32_dpp v25, v43 row_shr:2 row_mask:0xf bank_mask:0xf
	v_pk_fma_f32 v[18:19], v[76:77], v[26:27], v[18:19]
	v_mov_b32_dpp v21, v43 row_shr:1 row_mask:0xf bank_mask:0xf
	v_pk_mul_f32 v[22:23], v[18:19], s[30:31] op_sel_hi:[1,0]
	v_lshlrev_b32_e32 v24, 16, v25
	v_med3_f32 v22, v22, s47, v225
	v_med3_f32 v23, v23, s47, v225
	v_pk_mul_f32 v[26:27], v[22:23], v[22:23]
	v_and_b32_e32 v25, 0xffff0000, v25
	v_pk_fma_f32 v[28:29], v[26:27], s[34:35], v[2:3] op_sel_hi:[1,0,0] neg_lo:[1,0,0] neg_hi:[1,0,0]
	v_pk_mul_f32 v[18:19], v[18:19], 0.5 op_sel_hi:[1,0]
	v_pk_fma_f32 v[28:29], v[26:27], v[28:29], s[38:39] op_sel_hi:[1,1,0]
	v_lshlrev_b32_e32 v20, 16, v21
	v_pk_fma_f32 v[28:29], v[26:27], v[28:29], s[40:41] op_sel_hi:[1,1,0]
	v_and_b32_e32 v21, 0xffff0000, v21
	v_pk_fma_f32 v[28:29], v[26:27], v[28:29], s[42:43] op_sel_hi:[1,1,0]
	v_mov_b32_dpp v1, v40 row_ror:1 row_mask:0xf bank_mask:0xf bound_ctrl:1
	v_pk_fma_f32 v[28:29], v[26:27], v[28:29], s[44:45] op_sel_hi:[1,1,0]
	s_nop 0
	v_pk_fma_f32 v[28:29], v[26:27], v[28:29], s[46:47] op_sel_hi:[1,1,0]
	v_mov_b32_dpp v1, v36 row_shr:1 row_mask:0xf bank_mask:0xf
	v_pk_fma_f32 v[26:27], v[26:27], v[28:29], s[48:49] op_sel_hi:[1,1,0]
	s_nop 0
	v_pk_mul_f32 v[22:23], v[22:23], v[26:27]
	s_nop 0
	v_pk_fma_f32 v[18:19], v[18:19], v[22:23], v[18:19]
	v_pk_fma_f32 v[22:23], v[66:67], v[24:25], v[82:83]
	v_pk_mul_f32 v[12:13], v[12:13], v[18:19]
	v_lshlrev_b32_e32 v18, 16, v43
	v_and_b32_e32 v19, 0xffff0000, v43
	v_pk_fma_f32 v[20:21], v[74:75], v[20:21], v[22:23]
	s_nop 0
	v_pk_fma_f32 v[18:19], v[78:79], v[18:19], v[20:21]
	s_nop 0
	v_pk_mul_f32 v[20:21], v[18:19], s[30:31] op_sel_hi:[1,0]
	v_pk_mul_f32 v[18:19], v[18:19], 0.5 op_sel_hi:[1,0]
	v_med3_f32 v20, v20, s47, v225
	v_med3_f32 v21, v21, s47, v225
	v_pk_mul_f32 v[22:23], v[20:21], v[20:21]
	s_nop 0
	v_pk_fma_f32 v[24:25], v[22:23], s[34:35], v[2:3] op_sel_hi:[1,0,0] neg_lo:[1,0,0] neg_hi:[1,0,0]
; __device__ __forceinline__ unsigned cvt_pk_bf16(float lo, float hi) { unsigned r; asm volatile("v_cvt_pk_bf16_f32 %0, %1, %2" : "=v"(r) : "v"(lo), "v"(hi)); return r; }
;     static __device__ __forceinline__ void unpk4(const u32x2 w, float (&o)[4]) { o[0] = bf_lo(w.x); o[1] = bf_hi(w.x); o[2] = bf_lo(w.y); o[3] = bf_hi(w.y); }
;     template <int N> static __device__ __forceinline__ u32x2 dpp_prev(const u32x2 pv, const u32x2 cur) { u32x2 r; r.x = dpp_prev1<N>(pv.x, cur.x); r.y = dpp_prev1<N>(pv.y, cur.y); return r; }
;     static __device__ __forceinline__ u32x2 finish2(const float (&g0)[4], const float (&g1)[4], const float (&g2)[4], const float (&w0)[4], const float (&w1)[4], const float (&w2)[4], const float (&bb)[4],
;                                                     const f32x4 v, float rs) {
;         float h[4];
; #pragma unroll
;         for (int j = 0; j < 4; j += 2) {
;             const f32x2 gc = (f32x2){bb[j] + w0[j] * g2[j] + w1[j] * g1[j] + w2[j] * g0[j], bb[j + 1] + w0[j + 1] * g2[j + 1] + w1[j + 1] * g1[j + 1] + w2[j + 1] * g0[j + 1]};
;             const f32x2 ge = gelu_pk(gc) * ((f32x2){v[j], v[j + 1]} * rs); h[j] = ge.x; h[j + 1] = ge.y; }
;         u32x2 w; w.x = cvt_pk_bf16(h[0], h[1]); w.y = cvt_pk_bf16(h[2], h[3]); return w;
;     }
;     __device__ __forceinline__ void operator()(const f32x4 (&acc)[2][2][4][2], const Unit& u, int wr, int wc, int fr, int fq) const {
;     ...
;                 for (int m = 0; m < 4; ++m) { const u32x4 cur = gq[m]; u32x4 hw;
; #pragma unroll
;                     for (int hv = 0; hv < 2; ++hv) { const u32x2 c2 = half2(cur, hv), p2 = half2(pv, hv);
;                         const u32x2 q1 = dpp_prev<1>(p2, c2), q2 = dpp_prev<2>(p2, c2);
;                         float g0[4], g1[4], g2[4]; unpk4(c2, g0); unpk4(q1, g1); unpk4(q2, g2);
;                         const u32x2 r = finish2(g0, g1, g2, w0[hv], w1[hv], w2[hv], bb[hv], acc[ai][bj][m][hv], rs8[ai][m]);
;                         if (hv == 0) { hw.x = r.x; hw.y = r.y; } else { hw.z = r.x; hw.w = r.y; } }
;                     *(u32x4*)(H + (size_t)(R0 + fr + 16 * m) * 2816 + col8) = hw;
	s_nop 0
	v_pk_fma_f32 v[24:25], v[22:23], v[24:25], s[38:39] op_sel_hi:[1,1,0]
	s_nop 0
	v_pk_fma_f32 v[24:25], v[22:23], v[24:25], s[40:41] op_sel_hi:[1,1,0]
	s_nop 0
	v_pk_fma_f32 v[24:25], v[22:23], v[24:25], s[42:43] op_sel_hi:[1,1,0]
	s_nop 0
	v_pk_fma_f32 v[24:25], v[22:23], v[24:25], s[44:45] op_sel_hi:[1,1,0]
	s_nop 0
	v_pk_fma_f32 v[24:25], v[22:23], v[24:25], s[46:47] op_sel_hi:[1,1,0]
	s_nop 0
	v_pk_fma_f32 v[22:23], v[22:23], v[24:25], s[48:49] op_sel_hi:[1,1,0]
	s_nop 0
	v_pk_mul_f32 v[20:21], v[20:21], v[22:23]
	s_nop 0
	v_pk_fma_f32 v[18:19], v[18:19], v[20:21], v[18:19]
	v_lshlrev_b32_e32 v20, 16, v36
	v_pk_mul_f32 v[14:15], v[14:15], v[18:19]
	v_cvt_pk_bf16_f32 v18, v12, v13
	v_lshl_add_u64 v[12:13], v[174:175], 0, v[60:61]
	v_cvt_pk_bf16_f32 v19, v14, v15
	global_store_dwordx4 v[12:13], v[16:19], off sc1
	v_lshlrev_b32_e32 v12, 16, v1
	v_and_b32_e32 v13, 0xffff0000, v1
	v_mov_b32_dpp v17, v40 row_ror:2 row_mask:0xf bank_mask:0xf bound_ctrl:1
	v_and_b32_e32 v21, 0xffff0000, v36
	v_mov_b32_dpp v19, v41 row_ror:2 row_mask:0xf bank_mask:0xf bound_ctrl:1
	v_mov_b32_dpp v17, v36 row_shr:2 row_mask:0xf bank_mask:0xf
	v_lshlrev_b32_e32 v16, 16, v17
	v_and_b32_e32 v17, 0xffff0000, v17
	v_pk_fma_f32 v[16:17], v[84:85], v[16:17], v[96:97]
	v_mov_b32_dpp v15, v41 row_ror:1 row_mask:0xf bank_mask:0xf bound_ctrl:1
	v_pk_fma_f32 v[12:13], v[88:89], v[12:13], v[16:17]
	v_mov_b32_dpp v19, v37 row_shr:2 row_mask:0xf bank_mask:0xf
	v_pk_fma_f32 v[12:13], v[92:93], v[20:21], v[12:13]
	v_mov_b32_dpp v15, v37 row_shr:1 row_mask:0xf bank_mask:0xf
	v_pk_mul_f32 v[16:17], v[12:13], s[30:31] op_sel_hi:[1,0]
	v_lshlrev_b32_e32 v18, 16, v19
	v_med3_f32 v16, v16, s47, v225
	v_med3_f32 v17, v17, s47, v225
	v_pk_mul_f32 v[20:21], v[16:17], v[16:17]
	v_and_b32_e32 v19, 0xffff0000, v19
	v_pk_fma_f32 v[22:23], v[20:21], s[34:35], v[2:3] op_sel_hi:[1,0,0] neg_lo:[1,0,0] neg_hi:[1,0,0]
	v_pk_mul_f32 v[12:13], v[12:13], 0.5 op_sel_hi:[1,0]
	v_pk_fma_f32 v[22:23], v[20:21], v[22:23], s[38:39] op_sel_hi:[1,1,0]
	v_lshlrev_b32_e32 v14, 16, v15
	v_pk_fma_f32 v[22:23], v[20:21], v[22:23], s[40:41] op_sel_hi:[1,1,0]
	v_and_b32_e32 v15, 0xffff0000, v15
	v_pk_fma_f32 v[22:23], v[20:21], v[22:23], s[42:43] op_sel_hi:[1,1,0]
	v_mov_b32_dpp v1, v42 row_ror:1 row_mask:0xf bank_mask:0xf bound_ctrl:1
	v_pk_fma_f32 v[22:23], v[20:21], v[22:23], s[44:45] op_sel_hi:[1,1,0]
	s_nop 0
	v_pk_fma_f32 v[22:23], v[20:21], v[22:23], s[46:47] op_sel_hi:[1,1,0]
	v_mov_b32_dpp v1, v38 row_shr:1 row_mask:0xf bank_mask:0xf
	v_pk_fma_f32 v[20:21], v[20:21], v[22:23], s[48:49] op_sel_hi:[1,1,0]
	s_nop 0
	v_pk_mul_f32 v[16:17], v[16:17], v[20:21]
	s_nop 0
	v_pk_fma_f32 v[12:13], v[12:13], v[16:17], v[12:13]
	v_pk_fma_f32 v[16:17], v[86:87], v[18:19], v[98:99]
	v_pk_mul_f32 v[8:9], v[8:9], v[12:13]
	v_lshlrev_b32_e32 v12, 16, v37
	v_and_b32_e32 v13, 0xffff0000, v37
	v_pk_fma_f32 v[14:15], v[90:91], v[14:15], v[16:17]
	v_cvt_pk_bf16_f32 v8, v8, v9
	s_nop 0
	v_pk_fma_f32 v[12:13], v[94:95], v[12:13], v[14:15]
	s_nop 0
	v_pk_mul_f32 v[14:15], v[12:13], s[30:31] op_sel_hi:[1,0]
	v_pk_mul_f32 v[12:13], v[12:13], 0.5 op_sel_hi:[1,0]
	v_med3_f32 v14, v14, s47, v225
	v_med3_f32 v15, v15, s47, v225
	v_pk_mul_f32 v[16:17], v[14:15], v[14:15]
	s_nop 0
	v_pk_fma_f32 v[18:19], v[16:17], s[34:35], v[2:3] op_sel_hi:[1,0,0] neg_lo:[1,0,0] neg_hi:[1,0,0]
	s_nop 0
	v_pk_fma_f32 v[18:19], v[16:17], v[18:19], s[38:39] op_sel_hi:[1,1,0]
	s_nop 0
	v_pk_fma_f32 v[18:19], v[16:17], v[18:19], s[40:41] op_sel_hi:[1,1,0]
	s_nop 0
	v_pk_fma_f32 v[18:19], v[16:17], v[18:19], s[42:43] op_sel_hi:[1,1,0]
; __device__ __forceinline__ unsigned cvt_pk_bf16(float lo, float hi) { unsigned r; asm volatile("v_cvt_pk_bf16_f32 %0, %1, %2" : "=v"(r) : "v"(lo), "v"(hi)); return r; }
;     static __device__ __forceinline__ void unpk4(const u32x2 w, float (&o)[4]) { o[0] = bf_lo(w.x); o[1] = bf_hi(w.x); o[2] = bf_lo(w.y); o[3] = bf_hi(w.y); }
;     template <int N> static __device__ __forceinline__ u32x2 dpp_prev(const u32x2 pv, const u32x2 cur) { u32x2 r; r.x = dpp_prev1<N>(pv.x, cur.x); r.y = dpp_prev1<N>(pv.y, cur.y); return r; }
;     static __device__ __forceinline__ u32x2 finish2(const float (&g0)[4], const float (&g1)[4], const float (&g2)[4], const float (&w0)[4], const float (&w1)[4], const float (&w2)[4], const float (&bb)[4],
;                                                     const f32x4 v, float rs) {
;         float h[4];
; #pragma unroll
;         for (int j = 0; j < 4; j += 2) {
;             const f32x2 gc = (f32x2){bb[j] + w0[j] * g2[j] + w1[j] * g1[j] + w2[j] * g0[j], bb[j + 1] + w0[j + 1] * g2[j + 1] + w1[j + 1] * g1[j + 1] + w2[j + 1] * g0[j + 1]};
;             const f32x2 ge = gelu_pk(gc) * ((f32x2){v[j], v[j + 1]} * rs); h[j] = ge.x; h[j + 1] = ge.y; }
;         u32x2 w; w.x = cvt_pk_bf16(h[0], h[1]); w.y = cvt_pk_bf16(h[2], h[3]); return w;
;     }
;     __device__ __forceinline__ void operator()(const f32x4 (&acc)[2][2][4][2], const Unit& u, int wr, int wc, int fr, int fq) const {
;     ...
;                 for (int m = 0; m < 4; ++m) { const u32x4 cur = gq[m]; u32x4 hw;
; #pragma unroll
;                     for (int hv = 0; hv < 2; ++hv) { const u32x2 c2 = half2(cur, hv), p2 = half2(pv, hv);
;                         const u32x2 q1 = dpp_prev<1>(p2, c2), q2 = dpp_prev<2>(p2, c2);
;                         float g0[4], g1[4], g2[4]; unpk4(c2, g0); unpk4(q1, g1); unpk4(q2, g2);
;                         const u32x2 r = finish2(g0, g1, g2, w0[hv], w1[hv], w2[hv], bb[hv], acc[ai][bj][m][hv], rs8[ai][m]);
;                         if (hv == 0) { hw.x = r.x; hw.y = r.y; } else { hw.z = r.x; hw.w = r.y; } }
;                     *(u32x4*)(H + (size_t)(R0 + fr + 16 * m) * 2816 + col8) = hw;
	s_nop 0
	v_pk_fma_f32 v[18:19], v[16:17], v[18:19], s[44:45] op_sel_hi:[1,1,0]
	s_nop 0
	v_pk_fma_f32 v[18:19], v[16:17], v[18:19], s[46:47] op_sel_hi:[1,1,0]
	s_nop 0
	v_pk_fma_f32 v[16:17], v[16:17], v[18:19], s[48:49] op_sel_hi:[1,1,0]
	v_lshlrev_b32_e32 v18, 16, v38
	v_pk_mul_f32 v[14:15], v[14:15], v[16:17]
	v_and_b32_e32 v19, 0xffff0000, v38
	v_pk_fma_f32 v[12:13], v[12:13], v[14:15], v[12:13]
	v_mov_b32_dpp v15, v42 row_ror:2 row_mask:0xf bank_mask:0xf bound_ctrl:1
	v_pk_mul_f32 v[10:11], v[10:11], v[12:13]
	v_mov_b32_dpp v17, v43 row_ror:2 row_mask:0xf bank_mask:0xf bound_ctrl:1
	v_mov_b32_dpp v15, v38 row_shr:2 row_mask:0xf bank_mask:0xf
	v_lshlrev_b32_e32 v14, 16, v15
	v_and_b32_e32 v15, 0xffff0000, v15
	v_cvt_pk_bf16_f32 v9, v10, v11
	v_lshlrev_b32_e32 v10, 16, v1
	v_and_b32_e32 v11, 0xffff0000, v1
	v_pk_fma_f32 v[14:15], v[64:65], v[14:15], v[80:81]
	v_mov_b32_dpp v13, v43 row_ror:1 row_mask:0xf bank_mask:0xf bound_ctrl:1
	v_pk_fma_f32 v[10:11], v[72:73], v[10:11], v[14:15]
	v_mov_b32_dpp v17, v39 row_shr:2 row_mask:0xf bank_mask:0xf
	v_pk_fma_f32 v[10:11], v[76:77], v[18:19], v[10:11]
	v_mov_b32_dpp v13, v39 row_shr:1 row_mask:0xf bank_mask:0xf
	v_pk_mul_f32 v[14:15], v[10:11], s[30:31] op_sel_hi:[1,0]
	v_lshlrev_b32_e32 v16, 16, v17
	v_med3_f32 v14, v14, s47, v225
	v_med3_f32 v15, v15, s47, v225
	v_pk_mul_f32 v[18:19], v[14:15], v[14:15]
	v_and_b32_e32 v17, 0xffff0000, v17
	v_pk_fma_f32 v[20:21], v[18:19], s[34:35], v[2:3] op_sel_hi:[1,0,0] neg_lo:[1,0,0] neg_hi:[1,0,0]
	v_pk_mul_f32 v[10:11], v[10:11], 0.5 op_sel_hi:[1,0]
	v_pk_fma_f32 v[20:21], v[18:19], v[20:21], s[38:39] op_sel_hi:[1,1,0]
	v_lshlrev_b32_e32 v12, 16, v13
	v_pk_fma_f32 v[20:21], v[18:19], v[20:21], s[40:41] op_sel_hi:[1,1,0]
	v_and_b32_e32 v13, 0xffff0000, v13
	v_pk_fma_f32 v[20:21], v[18:19], v[20:21], s[42:43] op_sel_hi:[1,1,0]
	s_nop 0
	v_pk_fma_f32 v[20:21], v[18:19], v[20:21], s[44:45] op_sel_hi:[1,1,0]
	s_nop 0
	v_pk_fma_f32 v[20:21], v[18:19], v[20:21], s[46:47] op_sel_hi:[1,1,0]
	s_nop 0
	v_pk_fma_f32 v[18:19], v[18:19], v[20:21], s[48:49] op_sel_hi:[1,1,0]
	s_nop 0
	v_pk_mul_f32 v[14:15], v[14:15], v[18:19]
	s_nop 0
	v_pk_fma_f32 v[10:11], v[10:11], v[14:15], v[10:11]
	v_pk_fma_f32 v[14:15], v[66:67], v[16:17], v[82:83]
	v_pk_mul_f32 v[4:5], v[4:5], v[10:11]
	v_lshlrev_b32_e32 v10, 16, v39
	v_and_b32_e32 v11, 0xffff0000, v39
	v_pk_fma_f32 v[12:13], v[74:75], v[12:13], v[14:15]
	s_nop 0
	v_pk_fma_f32 v[10:11], v[78:79], v[10:11], v[12:13]
	s_nop 0
	v_pk_mul_f32 v[12:13], v[10:11], s[30:31] op_sel_hi:[1,0]
	v_pk_mul_f32 v[10:11], v[10:11], 0.5 op_sel_hi:[1,0]
	v_med3_f32 v12, v12, s47, v225
	v_med3_f32 v13, v13, s47, v225
	v_pk_mul_f32 v[14:15], v[12:13], v[12:13]
	s_nop 0
	v_pk_fma_f32 v[2:3], v[14:15], s[34:35], v[2:3] op_sel_hi:[1,0,0] neg_lo:[1,0,0] neg_hi:[1,0,0]
	s_nop 0
	v_pk_fma_f32 v[2:3], v[14:15], v[2:3], s[38:39] op_sel_hi:[1,1,0]
	s_nop 0
	v_pk_fma_f32 v[2:3], v[14:15], v[2:3], s[40:41] op_sel_hi:[1,1,0]
	s_nop 0
	v_pk_fma_f32 v[2:3], v[14:15], v[2:3], s[42:43] op_sel_hi:[1,1,0]
	s_nop 0
	v_pk_fma_f32 v[2:3], v[14:15], v[2:3], s[44:45] op_sel_hi:[1,1,0]
	s_nop 0
	v_pk_fma_f32 v[2:3], v[14:15], v[2:3], s[46:47] op_sel_hi:[1,1,0]
	s_nop 0
	v_pk_fma_f32 v[2:3], v[14:15], v[2:3], s[48:49] op_sel_hi:[1,1,0]
	s_nop 0
	v_pk_mul_f32 v[2:3], v[12:13], v[2:3]
	s_nop 0
	v_pk_fma_f32 v[2:3], v[10:11], v[2:3], v[10:11]
	v_cvt_pk_bf16_f32 v10, v4, v5
	s_nop 0
	v_pk_mul_f32 v[2:3], v[6:7], v[2:3]
	s_nop 0
	v_cvt_pk_bf16_f32 v11, v2, v3
	v_lshl_add_u64 v[2:3], v[132:133], 0, v[60:61]
	global_store_dwordx4 v[2:3], v[8:11], off sc1

; __device__ __forceinline__ unsigned cvt_pk_bf16(float lo, float hi) { unsigned r; asm volatile("v_cvt_pk_bf16_f32 %0, %1, %2" : "=v"(r) : "v"(lo), "v"(hi)); return r; }
;     __device__ __forceinline__ void row_out(const f32x4 v0, const f32x4 v1, int row, int col, float& ss) const {
;         if (C) { float* rowp = C + (size_t)row * ldc + col; __builtin_nontemporal_store(v0, (f32x4*)rowp); __builtin_nontemporal_store(v1, (f32x4*)(rowp + 4)); }
;         if (wxb) { u32x4 w; w.x = cvt_pk_bf16(v0[0], v0[1]); w.y = cvt_pk_bf16(v0[2], v0[3]); w.z = cvt_pk_bf16(v1[0], v1[1]); w.w = cvt_pk_bf16(v1[2], v1[3]);
;             *(u32x4*)(XB0 + (size_t)row * ldc + col) = w;
;             ss += (v0[0] * v0[0] + v0[1] * v0[1]) + (v0[2] * v0[2] + v0[3] * v0[3]) + (v1[0] * v1[0] + v1[1] * v1[1]) + (v1[2] * v1[2] + v1[3] * v1[3]); }
;     }
;     __device__ __forceinline__ void operator()(const f32x4 (&acc)[2][2][4][2], const Unit& u, int wr, int wc, int fr, int fq) const {
;     ...
;               for (int mh = 0; mh < 4; mh += 2) {
;                 u32x4 rw[2][2];
; #pragma unroll
;                 for (int mm = 0; mm < 2; ++mm) { const int row = row0 + ai * HALF + (mh + mm) * 16;
; #pragma unroll
;                     for (int bj = 0; bj < 2; ++bj) if (bj == 0 || !u.q) rw[mm][bj] = *(const u32x4*)(XB0 + (size_t)row * ldc + col0 + bj * HALF); }
; #pragma unroll
;                 for (int mm = 0; mm < 2; ++mm) { const int m = mh + mm, row = row0 + ai * HALF + m * 16; float ss = 0.f;
; #pragma unroll
;                     for (int bj = 0; bj < 2; ++bj) if (bj == 0 || !u.q) { const u32x4 w = rw[mm][bj];
;                         const f32x4 v0 = acc[ai][bj][m][0] + (f32x4){bf_lo(w.x), bf_hi(w.x), bf_lo(w.y), bf_hi(w.y)}, v1 = acc[ai][bj][m][1] + (f32x4){bf_lo(w.z), bf_hi(w.z), bf_lo(w.w), bf_hi(w.w)};
;                         row_out(v0, v1, row, col0 + bj * HALF, ss); }
;                     if (wxb) { ss += __shfl_xor(ss, 16); ss += __shfl_xor(ss, 32); if (fq == 0) unsafeAtomicAdd(SS + row, ss); } }
.LBB0_1104:
	v_mov_b32_e32 v128, v163
	v_mov_b32_e32 v129, v162
	s_add_i32 s0, s47, s37
	s_nop 0
	v_add_u32_e32 v154, s0, v128
	s_add_i32 s0, s46, s38
	v_lshl_add_u32 v152, v129, 3, s0
	v_ashrrev_i32_e32 v153, 31, v152
	v_lshlrev_b64 v[178:179], 1, v[152:153]
	v_ashrrev_i32_e32 v155, 31, v154
	v_lshl_add_u64 v[156:157], s[96:97], 0, v[178:179]
	v_lshlrev_b64 v[180:181], 11, v[154:155]
	v_cmp_eq_u32_e32 vcc, 0, v129
	v_lshl_add_u64 v[128:129], v[156:157], 0, v[180:181]
	global_load_dwordx4 v[170:173], v[128:129], off
	global_load_dwordx4 v[174:177], v[128:129], off offset:256
	v_add_u32_e32 v158, 16, v154
	v_ashrrev_i32_e32 v159, 31, v158
	v_lshlrev_b64 v[160:161], 11, v[158:159]
	v_lshl_add_u64 v[128:129], v[156:157], 0, v[160:161]
	global_load_dwordx4 v[132:135], v[128:129], off
	s_nop 0
	global_load_dwordx4 v[128:131], v[128:129], off offset:256
	v_lshl_add_u64 v[180:181], s[96:97], 0, v[180:181]
	v_lshl_add_u64 v[178:179], v[180:181], 0, v[178:179]
	s_waitcnt vmcnt(0)
	v_lshlrev_b32_e32 v182, 16, v170
	v_and_b32_e32 v183, 0xffff0000, v170
	v_lshlrev_b32_e32 v170, 16, v171
	v_and_b32_e32 v171, 0xffff0000, v171
	v_pk_add_f32 v[126:127], v[126:127], v[170:171]
	v_lshlrev_b32_e32 v170, 16, v172
	v_and_b32_e32 v171, 0xffff0000, v172
	v_pk_add_f32 v[124:125], v[124:125], v[182:183]
	v_lshlrev_b32_e32 v172, 16, v173
	v_and_b32_e32 v173, 0xffff0000, v173
	v_pk_add_f32 v[170:171], v[120:121], v[170:171]
	v_cvt_pk_bf16_f32 v120, v124, v125
	v_cvt_pk_bf16_f32 v121, v126, v127
	v_pk_add_f32 v[172:173], v[122:123], v[172:173]
	v_cvt_pk_bf16_f32 v122, v170, v171
	s_nop 0
	v_cvt_pk_bf16_f32 v123, v172, v173
	global_store_dwordx4 v[178:179], v[120:123], off sc1
	s_nop 1
	v_mul_f32_e32 v120, v125, v125
	v_mul_f32_e32 v121, v127, v127
	v_fmac_f32_e32 v120, v124, v124
	v_fmac_f32_e32 v121, v126, v126
	v_add_f32_e32 v120, v120, v121
	v_mul_f32_e32 v121, v171, v171
	v_fmac_f32_e32 v121, v170, v170
	v_add_f32_e32 v120, v121, v120
	v_mul_f32_e32 v121, v173, v173
	v_fmac_f32_e32 v121, v172, v172
	v_add_f32_e32 v124, v121, v120
	v_lshlrev_b32_e32 v120, 16, v174
	v_and_b32_e32 v121, 0xffff0000, v174
	v_lshlrev_b32_e32 v122, 16, v175
	v_and_b32_e32 v123, 0xffff0000, v175
	v_pk_add_f32 v[118:119], v[118:119], v[122:123]
	v_pk_add_f32 v[116:117], v[116:117], v[120:121]
	v_lshlrev_b32_e32 v120, 16, v176
	v_and_b32_e32 v121, 0xffff0000, v176
	v_lshlrev_b32_e32 v122, 16, v177
	v_and_b32_e32 v123, 0xffff0000, v177
	v_pk_add_f32 v[122:123], v[114:115], v[122:123]
	v_pk_add_f32 v[120:121], v[112:113], v[120:121]
	v_cvt_pk_bf16_f32 v112, v116, v117
	v_cvt_pk_bf16_f32 v113, v118, v119
	s_nop 0
	v_cvt_pk_bf16_f32 v114, v120, v121
	v_cvt_pk_bf16_f32 v115, v122, v123
	global_store_dwordx4 v[178:179], v[112:115], off offset:256 sc1
	s_nop 1
	v_mul_f32_e32 v114, v117, v117
	v_mul_f32_e32 v115, v119, v119
	v_mul_f32_e32 v113, v121, v121
	v_fmac_f32_e32 v114, v116, v116
	v_fmac_f32_e32 v115, v118, v118
	v_mul_f32_e32 v112, v123, v123
	v_fmac_f32_e32 v113, v120, v120
	v_add_f32_e32 v114, v114, v115
	v_fmac_f32_e32 v112, v122, v122
	v_add_f32_e32 v113, v113, v114
	v_add_f32_e32 v112, v112, v113
	v_and_b32_e32 v114, 64, v168
	v_add_f32_e32 v113, v124, v112
	v_xor_b32_e32 v112, 16, v168
	v_add_u32_e32 v115, 64, v114
	v_cmp_lt_i32_e64 s[0:1], v112, v115
	s_nop 1
	v_cndmask_b32_e64 v112, v168, v112, s[0:1]
	v_lshlrev_b32_e32 v112, 2, v112
	ds_bpermute_b32 v114, v112, v113
	s_waitcnt lgkmcnt(0)
	v_add_f32_e32 v114, v113, v114
	v_xor_b32_e32 v113, 32, v168
	v_cmp_lt_i32_e64 s[0:1], v113, v115
	s_nop 1
	v_cndmask_b32_e64 v113, v168, v113, s[0:1]
	v_lshlrev_b32_e32 v113, 2, v113
	ds_bpermute_b32 v115, v113, v114
	s_and_saveexec_b64 s[0:1], vcc
	s_cbranch_execz .LBB0_1106
	s_waitcnt lgkmcnt(0)
	v_add_f32_e32 v116, v114, v115
	v_lshl_add_u64 v[114:115], v[154:155], 2, s[10:11]
	global_atomic_add_f32 v[114:115], v116, off
.LBB0_1106:
	s_or_b64 exec, exec, s[0:1]
	v_lshlrev_b32_e32 v114, 16, v132
	s_waitcnt lgkmcnt(0)
	v_and_b32_e32 v115, 0xffff0000, v132
	v_lshlrev_b32_e32 v116, 16, v133
	v_and_b32_e32 v117, 0xffff0000, v133
	v_pk_add_f32 v[108:109], v[108:109], v[114:115]
	v_lshlrev_b32_e32 v114, 16, v134
	v_and_b32_e32 v115, 0xffff0000, v134
	v_pk_add_f32 v[110:111], v[110:111], v[116:117]
	v_pk_add_f32 v[114:115], v[104:105], v[114:115]
	v_cvt_pk_bf16_f32 v104, v108, v109
	v_mul_f32_e32 v109, v109, v109
	v_fmac_f32_e32 v109, v108, v108
	v_mul_f32_e32 v108, v111, v111
	v_fmac_f32_e32 v108, v110, v110
	v_lshlrev_b32_e32 v116, 16, v135
	v_and_b32_e32 v117, 0xffff0000, v135
	v_add_f32_e32 v108, v109, v108
	v_mul_f32_e32 v109, v115, v115
	v_pk_add_f32 v[116:117], v[106:107], v[116:117]
	v_fmac_f32_e32 v109, v114, v114
	v_add_f32_e32 v108, v109, v108
	v_mul_f32_e32 v109, v117, v117
	v_fmac_f32_e32 v109, v116, v116
	v_cvt_pk_bf16_f32 v105, v110, v111
	v_cvt_pk_bf16_f32 v106, v114, v115
	v_add_f32_e32 v114, v109, v108
	v_lshlrev_b32_e32 v108, 16, v128
	v_and_b32_e32 v109, 0xffff0000, v128
	v_lshlrev_b32_e32 v110, 16, v129
	v_and_b32_e32 v111, 0xffff0000, v129
	v_pk_add_f32 v[102:103], v[102:103], v[110:111]
	v_pk_add_f32 v[100:101], v[100:101], v[108:109]
	v_lshlrev_b32_e32 v108, 16, v130
	v_and_b32_e32 v109, 0xffff0000, v130
	v_lshlrev_b32_e32 v110, 16, v131
	v_and_b32_e32 v111, 0xffff0000, v131
	v_pk_add_f32 v[110:111], v[98:99], v[110:111]
	v_pk_add_f32 v[108:109], v[96:97], v[108:109]
	v_mul_f32_e32 v98, v101, v101
	v_mul_f32_e32 v99, v103, v103
	v_mul_f32_e32 v97, v109, v109
	v_fmac_f32_e32 v98, v100, v100
	v_fmac_f32_e32 v99, v102, v102
	v_mul_f32_e32 v96, v111, v111
	v_fmac_f32_e32 v97, v108, v108
	v_add_f32_e32 v98, v98, v99
	v_fmac_f32_e32 v96, v110, v110
	v_add_f32_e32 v97, v97, v98
	v_add_f32_e32 v96, v96, v97
	v_add_f32_e32 v99, v114, v96
	v_cvt_pk_bf16_f32 v107, v116, v117
	ds_bpermute_b32 v116, v112, v99
	v_lshl_add_u64 v[96:97], s[96:97], 0, v[160:161]
	v_lshl_add_u64 v[114:115], v[152:153], 1, v[96:97]
	global_store_dwordx4 v[114:115], v[104:107], off sc1
	v_cvt_pk_bf16_f32 v98, v100, v101
	s_waitcnt lgkmcnt(0)
	v_add_f32_e32 v96, v99, v116
	ds_bpermute_b32 v97, v113, v96
	v_cvt_pk_bf16_f32 v99, v102, v103
	v_cvt_pk_bf16_f32 v100, v108, v109
	v_cvt_pk_bf16_f32 v101, v110, v111
	global_store_dwordx4 v[114:115], v[98:101], off offset:256 sc1
	s_and_saveexec_b64 s[0:1], vcc
	s_cbranch_execz .LBB0_1108
	s_waitcnt lgkmcnt(0)
	v_add_f32_e32 v98, v96, v97
	v_lshl_add_u64 v[96:97], v[158:159], 2, s[10:11]
	global_atomic_add_f32 v[96:97], v98, off
; __device__ __forceinline__ unsigned cvt_pk_bf16(float lo, float hi) { unsigned r; asm volatile("v_cvt_pk_bf16_f32 %0, %1, %2" : "=v"(r) : "v"(lo), "v"(hi)); return r; }
;     __device__ __forceinline__ void row_out(const f32x4 v0, const f32x4 v1, int row, int col, float& ss) const {
;         if (C) { float* rowp = C + (size_t)row * ldc + col; __builtin_nontemporal_store(v0, (f32x4*)rowp); __builtin_nontemporal_store(v1, (f32x4*)(rowp + 4)); }
;         if (wxb) { u32x4 w; w.x = cvt_pk_bf16(v0[0], v0[1]); w.y = cvt_pk_bf16(v0[2], v0[3]); w.z = cvt_pk_bf16(v1[0], v1[1]); w.w = cvt_pk_bf16(v1[2], v1[3]);
;             *(u32x4*)(XB0 + (size_t)row * ldc + col) = w;
;             ss += (v0[0] * v0[0] + v0[1] * v0[1]) + (v0[2] * v0[2] + v0[3] * v0[3]) + (v1[0] * v1[0] + v1[1] * v1[1]) + (v1[2] * v1[2] + v1[3] * v1[3]); }
;     }
;     __device__ __forceinline__ void operator()(const f32x4 (&acc)[2][2][4][2], const Unit& u, int wr, int wc, int fr, int fq) const {
;     ...
;               for (int mh = 0; mh < 4; mh += 2) {
;                 u32x4 rw[2][2];
; #pragma unroll
;                 for (int mm = 0; mm < 2; ++mm) { const int row = row0 + ai * HALF + (mh + mm) * 16;
; #pragma unroll
;                     for (int bj = 0; bj < 2; ++bj) if (bj == 0 || !u.q) rw[mm][bj] = *(const u32x4*)(XB0 + (size_t)row * ldc + col0 + bj * HALF); }
; #pragma unroll
;                 for (int mm = 0; mm < 2; ++mm) { const int m = mh + mm, row = row0 + ai * HALF + m * 16; float ss = 0.f;
; #pragma unroll
;                     for (int bj = 0; bj < 2; ++bj) if (bj == 0 || !u.q) { const u32x4 w = rw[mm][bj];
;                         const f32x4 v0 = acc[ai][bj][m][0] + (f32x4){bf_lo(w.x), bf_hi(w.x), bf_lo(w.y), bf_hi(w.y)}, v1 = acc[ai][bj][m][1] + (f32x4){bf_lo(w.z), bf_hi(w.z), bf_lo(w.w), bf_hi(w.w)};
;                         row_out(v0, v1, row, col0 + bj * HALF, ss); }
;                     if (wxb) { ss += __shfl_xor(ss, 16); ss += __shfl_xor(ss, 32); if (fq == 0) unsafeAtomicAdd(SS + row, ss); } }
.LBB0_1108:
	s_or_b64 exec, exec, s[0:1]
	v_add_u32_e32 v108, 32, v154
	v_ashrrev_i32_e32 v109, 31, v108
	v_lshlrev_b64 v[110:111], 11, v[108:109]
	s_waitcnt lgkmcnt(0)
	v_lshl_add_u64 v[96:97], v[156:157], 0, v[110:111]
	global_load_dwordx4 v[114:117], v[96:97], off
	global_load_dwordx4 v[118:121], v[96:97], off offset:256
	v_add_u32_e32 v104, 48, v154
	v_ashrrev_i32_e32 v105, 31, v104
	v_lshlrev_b64 v[106:107], 11, v[104:105]
	v_lshl_add_u64 v[96:97], v[156:157], 0, v[106:107]
	global_load_dwordx4 v[100:103], v[96:97], off
	s_nop 0
	global_load_dwordx4 v[96:99], v[96:97], off offset:256
	v_lshl_add_u64 v[110:111], s[96:97], 0, v[110:111]
	v_lshl_add_u64 v[110:111], v[152:153], 1, v[110:111]
	s_waitcnt vmcnt(3)
	v_lshlrev_b32_e32 v122, 16, v114
	v_and_b32_e32 v123, 0xffff0000, v114
	v_lshlrev_b32_e32 v114, 16, v115
	v_and_b32_e32 v115, 0xffff0000, v115
	v_pk_add_f32 v[94:95], v[94:95], v[114:115]
	v_lshlrev_b32_e32 v114, 16, v116
	v_and_b32_e32 v115, 0xffff0000, v116
	v_pk_add_f32 v[92:93], v[92:93], v[122:123]
	v_lshlrev_b32_e32 v116, 16, v117
	v_and_b32_e32 v117, 0xffff0000, v117
	v_pk_add_f32 v[114:115], v[88:89], v[114:115]
	v_cvt_pk_bf16_f32 v88, v92, v93
	v_cvt_pk_bf16_f32 v89, v94, v95
	v_pk_add_f32 v[116:117], v[90:91], v[116:117]
	v_cvt_pk_bf16_f32 v90, v114, v115
	s_nop 0
	v_cvt_pk_bf16_f32 v91, v116, v117
	global_store_dwordx4 v[110:111], v[88:91], off sc1
	s_nop 1
	v_mul_f32_e32 v88, v93, v93
	v_mul_f32_e32 v89, v95, v95
	v_fmac_f32_e32 v88, v92, v92
	v_fmac_f32_e32 v89, v94, v94
	v_add_f32_e32 v88, v88, v89
	v_mul_f32_e32 v89, v115, v115
	v_fmac_f32_e32 v89, v114, v114
	v_add_f32_e32 v88, v89, v88
	v_mul_f32_e32 v89, v117, v117
	v_fmac_f32_e32 v89, v116, v116
	v_add_f32_e32 v92, v89, v88
	s_waitcnt vmcnt(3)
	v_lshlrev_b32_e32 v88, 16, v118
	v_and_b32_e32 v89, 0xffff0000, v118
	v_lshlrev_b32_e32 v90, 16, v119
	v_and_b32_e32 v91, 0xffff0000, v119
	v_pk_add_f32 v[86:87], v[86:87], v[90:91]
	v_pk_add_f32 v[84:85], v[84:85], v[88:89]
	v_lshlrev_b32_e32 v88, 16, v120
	v_and_b32_e32 v89, 0xffff0000, v120
	v_lshlrev_b32_e32 v90, 16, v121
	v_and_b32_e32 v91, 0xffff0000, v121
	v_pk_add_f32 v[90:91], v[82:83], v[90:91]
	v_pk_add_f32 v[88:89], v[80:81], v[88:89]
	v_cvt_pk_bf16_f32 v80, v84, v85
	v_cvt_pk_bf16_f32 v81, v86, v87
	s_nop 0
	v_cvt_pk_bf16_f32 v82, v88, v89
	v_cvt_pk_bf16_f32 v83, v90, v91
	global_store_dwordx4 v[110:111], v[80:83], off offset:256 sc1
	s_nop 1
	v_mul_f32_e32 v82, v85, v85
	v_mul_f32_e32 v83, v87, v87
	v_mul_f32_e32 v81, v89, v89
	v_fmac_f32_e32 v82, v84, v84
	v_fmac_f32_e32 v83, v86, v86
	v_mul_f32_e32 v80, v91, v91
	v_fmac_f32_e32 v81, v88, v88
	v_add_f32_e32 v82, v82, v83
	v_fmac_f32_e32 v80, v90, v90
	v_add_f32_e32 v81, v81, v82
	v_add_f32_e32 v80, v80, v81
	v_add_f32_e32 v80, v92, v80
	ds_bpermute_b32 v81, v112, v80
	s_waitcnt lgkmcnt(0)
	v_add_f32_e32 v80, v80, v81
	ds_bpermute_b32 v81, v113, v80
	s_and_saveexec_b64 s[0:1], vcc
	s_cbranch_execz .LBB0_1110
	s_waitcnt lgkmcnt(0)
	v_add_f32_e32 v82, v80, v81
	v_lshl_add_u64 v[80:81], v[108:109], 2, s[10:11]
	global_atomic_add_f32 v[80:81], v82, off
.LBB0_1110:
	s_or_b64 exec, exec, s[0:1]
	s_waitcnt vmcnt(3)
	v_lshlrev_b32_e32 v80, 16, v100
	s_waitcnt lgkmcnt(0)
	v_and_b32_e32 v81, 0xffff0000, v100
	v_lshlrev_b32_e32 v82, 16, v101
	v_and_b32_e32 v83, 0xffff0000, v101
	v_pk_add_f32 v[76:77], v[76:77], v[80:81]
	v_lshlrev_b32_e32 v80, 16, v102
	v_and_b32_e32 v81, 0xffff0000, v102
	v_pk_add_f32 v[78:79], v[78:79], v[82:83]
	v_pk_add_f32 v[80:81], v[72:73], v[80:81]
	v_cvt_pk_bf16_f32 v72, v76, v77
	v_mul_f32_e32 v77, v77, v77
	v_fmac_f32_e32 v77, v76, v76
	v_mul_f32_e32 v76, v79, v79
	v_fmac_f32_e32 v76, v78, v78
	v_lshlrev_b32_e32 v82, 16, v103
	v_and_b32_e32 v83, 0xffff0000, v103
	v_add_f32_e32 v76, v77, v76
	v_mul_f32_e32 v77, v81, v81
	v_pk_add_f32 v[82:83], v[74:75], v[82:83]
	v_fmac_f32_e32 v77, v80, v80
	v_add_f32_e32 v76, v77, v76
	v_mul_f32_e32 v77, v83, v83
	v_fmac_f32_e32 v77, v82, v82
	v_cvt_pk_bf16_f32 v73, v78, v79
	v_cvt_pk_bf16_f32 v74, v80, v81
	v_add_f32_e32 v80, v77, v76
	s_waitcnt vmcnt(2)
	v_lshlrev_b32_e32 v76, 16, v96
	v_and_b32_e32 v77, 0xffff0000, v96
	v_lshlrev_b32_e32 v78, 16, v97
	v_and_b32_e32 v79, 0xffff0000, v97
	v_pk_add_f32 v[70:71], v[70:71], v[78:79]
	v_pk_add_f32 v[68:69], v[68:69], v[76:77]
	v_lshlrev_b32_e32 v76, 16, v98
	v_and_b32_e32 v77, 0xffff0000, v98
	v_lshlrev_b32_e32 v78, 16, v99
	v_and_b32_e32 v79, 0xffff0000, v99
	v_pk_add_f32 v[78:79], v[66:67], v[78:79]
	v_pk_add_f32 v[76:77], v[64:65], v[76:77]
	v_mul_f32_e32 v66, v69, v69
	v_mul_f32_e32 v67, v71, v71
	v_mul_f32_e32 v65, v77, v77
	v_fmac_f32_e32 v66, v68, v68
	v_fmac_f32_e32 v67, v70, v70
	v_mul_f32_e32 v64, v79, v79
	v_fmac_f32_e32 v65, v76, v76
	v_add_f32_e32 v66, v66, v67
	v_fmac_f32_e32 v64, v78, v78
	v_add_f32_e32 v65, v65, v66
	v_add_f32_e32 v64, v64, v65
	v_add_f32_e32 v67, v80, v64
	v_cvt_pk_bf16_f32 v75, v82, v83
	ds_bpermute_b32 v82, v112, v67
	v_lshl_add_u64 v[64:65], s[96:97], 0, v[106:107]
	v_lshl_add_u64 v[80:81], v[152:153], 1, v[64:65]
	global_store_dwordx4 v[80:81], v[72:75], off sc1
	v_cvt_pk_bf16_f32 v66, v68, v69
	s_waitcnt lgkmcnt(0)
	v_add_f32_e32 v64, v67, v82
	ds_bpermute_b32 v65, v113, v64
	v_cvt_pk_bf16_f32 v67, v70, v71
	v_cvt_pk_bf16_f32 v68, v76, v77
	v_cvt_pk_bf16_f32 v69, v78, v79
	global_store_dwordx4 v[80:81], v[66:69], off offset:256 sc1
	s_and_saveexec_b64 s[0:1], vcc
	s_cbranch_execz .LBB0_1112
	s_waitcnt lgkmcnt(0)
	v_add_f32_e32 v66, v64, v65
	v_lshl_add_u64 v[64:65], v[104:105], 2, s[10:11]
	global_atomic_add_f32 v[64:65], v66, off
; __device__ __forceinline__ unsigned cvt_pk_bf16(float lo, float hi) { unsigned r; asm volatile("v_cvt_pk_bf16_f32 %0, %1, %2" : "=v"(r) : "v"(lo), "v"(hi)); return r; }
;     __device__ __forceinline__ void row_out(const f32x4 v0, const f32x4 v1, int row, int col, float& ss) const {
;         if (C) { float* rowp = C + (size_t)row * ldc + col; __builtin_nontemporal_store(v0, (f32x4*)rowp); __builtin_nontemporal_store(v1, (f32x4*)(rowp + 4)); }
;         if (wxb) { u32x4 w; w.x = cvt_pk_bf16(v0[0], v0[1]); w.y = cvt_pk_bf16(v0[2], v0[3]); w.z = cvt_pk_bf16(v1[0], v1[1]); w.w = cvt_pk_bf16(v1[2], v1[3]);
;             *(u32x4*)(XB0 + (size_t)row * ldc + col) = w;
;             ss += (v0[0] * v0[0] + v0[1] * v0[1]) + (v0[2] * v0[2] + v0[3] * v0[3]) + (v1[0] * v1[0] + v1[1] * v1[1]) + (v1[2] * v1[2] + v1[3] * v1[3]); }
;     }
;     __device__ __forceinline__ void operator()(const f32x4 (&acc)[2][2][4][2], const Unit& u, int wr, int wc, int fr, int fq) const {
;     ...
;               for (int mh = 0; mh < 4; mh += 2) {
;                 u32x4 rw[2][2];
; #pragma unroll
;                 for (int mm = 0; mm < 2; ++mm) { const int row = row0 + ai * HALF + (mh + mm) * 16;
; #pragma unroll
;                     for (int bj = 0; bj < 2; ++bj) if (bj == 0 || !u.q) rw[mm][bj] = *(const u32x4*)(XB0 + (size_t)row * ldc + col0 + bj * HALF); }
; #pragma unroll
;                 for (int mm = 0; mm < 2; ++mm) { const int m = mh + mm, row = row0 + ai * HALF + m * 16; float ss = 0.f;
; #pragma unroll
;                     for (int bj = 0; bj < 2; ++bj) if (bj == 0 || !u.q) { const u32x4 w = rw[mm][bj];
;                         const f32x4 v0 = acc[ai][bj][m][0] + (f32x4){bf_lo(w.x), bf_hi(w.x), bf_lo(w.y), bf_hi(w.y)}, v1 = acc[ai][bj][m][1] + (f32x4){bf_lo(w.z), bf_hi(w.z), bf_lo(w.w), bf_hi(w.w)};
;                         row_out(v0, v1, row, col0 + bj * HALF, ss); }
;                     if (wxb) { ss += __shfl_xor(ss, 16); ss += __shfl_xor(ss, 32); if (fq == 0) unsafeAtomicAdd(SS + row, ss); } }
.LBB0_1112:
	s_or_b64 exec, exec, s[0:1]
	v_add_u32_e32 v76, 0x80, v154
	v_ashrrev_i32_e32 v77, 31, v76
	v_lshlrev_b64 v[86:87], 11, v[76:77]
	s_waitcnt lgkmcnt(0)
	v_lshl_add_u64 v[64:65], v[156:157], 0, v[86:87]
	global_load_dwordx4 v[78:81], v[64:65], off
	global_load_dwordx4 v[82:85], v[64:65], off offset:256
	v_add_u32_e32 v72, 0x90, v154
	v_ashrrev_i32_e32 v73, 31, v72
	v_lshlrev_b64 v[74:75], 11, v[72:73]
	v_lshl_add_u64 v[64:65], v[156:157], 0, v[74:75]
	global_load_dwordx4 v[68:71], v[64:65], off
	s_nop 0
	global_load_dwordx4 v[64:67], v[64:65], off offset:256
	v_lshl_add_u64 v[86:87], s[96:97], 0, v[86:87]
	v_lshl_add_u64 v[86:87], v[152:153], 1, v[86:87]
	s_waitcnt vmcnt(3)
	v_lshlrev_b32_e32 v88, 16, v78
	v_and_b32_e32 v89, 0xffff0000, v78
	v_lshlrev_b32_e32 v78, 16, v79
	v_and_b32_e32 v79, 0xffff0000, v79
	v_pk_add_f32 v[62:63], v[62:63], v[78:79]
	v_lshlrev_b32_e32 v78, 16, v80
	v_and_b32_e32 v79, 0xffff0000, v80
	v_pk_add_f32 v[60:61], v[60:61], v[88:89]
	v_lshlrev_b32_e32 v80, 16, v81
	v_and_b32_e32 v81, 0xffff0000, v81
	v_pk_add_f32 v[78:79], v[56:57], v[78:79]
	v_cvt_pk_bf16_f32 v56, v60, v61
	v_cvt_pk_bf16_f32 v57, v62, v63
	v_pk_add_f32 v[80:81], v[58:59], v[80:81]
	v_cvt_pk_bf16_f32 v58, v78, v79
	s_nop 0
	v_cvt_pk_bf16_f32 v59, v80, v81
	global_store_dwordx4 v[86:87], v[56:59], off sc1
	s_nop 1
	v_mul_f32_e32 v56, v61, v61
	v_mul_f32_e32 v57, v63, v63
	v_fmac_f32_e32 v56, v60, v60
	v_fmac_f32_e32 v57, v62, v62
	v_add_f32_e32 v56, v56, v57
	v_mul_f32_e32 v57, v79, v79
	v_fmac_f32_e32 v57, v78, v78
	v_add_f32_e32 v56, v57, v56
	v_mul_f32_e32 v57, v81, v81
	v_fmac_f32_e32 v57, v80, v80
	v_add_f32_e32 v60, v57, v56
	s_waitcnt vmcnt(3)
	v_lshlrev_b32_e32 v56, 16, v82
	v_and_b32_e32 v57, 0xffff0000, v82
	v_lshlrev_b32_e32 v58, 16, v83
	v_and_b32_e32 v59, 0xffff0000, v83
	v_pk_add_f32 v[54:55], v[54:55], v[58:59]
	v_pk_add_f32 v[52:53], v[52:53], v[56:57]
	v_lshlrev_b32_e32 v56, 16, v84
	v_and_b32_e32 v57, 0xffff0000, v84
	v_lshlrev_b32_e32 v58, 16, v85
	v_and_b32_e32 v59, 0xffff0000, v85
	v_pk_add_f32 v[58:59], v[50:51], v[58:59]
	v_pk_add_f32 v[56:57], v[48:49], v[56:57]
	v_cvt_pk_bf16_f32 v48, v52, v53
	v_cvt_pk_bf16_f32 v49, v54, v55
	s_nop 0
	v_cvt_pk_bf16_f32 v50, v56, v57
	v_cvt_pk_bf16_f32 v51, v58, v59
	global_store_dwordx4 v[86:87], v[48:51], off offset:256 sc1
	s_nop 1
	v_mul_f32_e32 v50, v53, v53
	v_mul_f32_e32 v51, v55, v55
	v_mul_f32_e32 v49, v57, v57
	v_fmac_f32_e32 v50, v52, v52
	v_fmac_f32_e32 v51, v54, v54
	v_mul_f32_e32 v48, v59, v59
	v_fmac_f32_e32 v49, v56, v56
	v_add_f32_e32 v50, v50, v51
	v_fmac_f32_e32 v48, v58, v58
	v_add_f32_e32 v49, v49, v50
	v_add_f32_e32 v48, v48, v49
	v_add_f32_e32 v48, v60, v48
	ds_bpermute_b32 v49, v112, v48
	s_waitcnt lgkmcnt(0)
	v_add_f32_e32 v48, v48, v49
	ds_bpermute_b32 v49, v113, v48
	s_and_saveexec_b64 s[0:1], vcc
	s_cbranch_execz .LBB0_1114
	s_waitcnt lgkmcnt(0)
	v_add_f32_e32 v50, v48, v49
	v_lshl_add_u64 v[48:49], v[76:77], 2, s[10:11]
	global_atomic_add_f32 v[48:49], v50, off
.LBB0_1114:
	s_or_b64 exec, exec, s[0:1]
	s_waitcnt vmcnt(3)
	v_lshlrev_b32_e32 v48, 16, v68
	s_waitcnt lgkmcnt(0)
	v_and_b32_e32 v49, 0xffff0000, v68
	v_lshlrev_b32_e32 v50, 16, v69
	v_and_b32_e32 v51, 0xffff0000, v69
	v_pk_add_f32 v[44:45], v[44:45], v[48:49]
	v_lshlrev_b32_e32 v48, 16, v70
	v_and_b32_e32 v49, 0xffff0000, v70
	v_pk_add_f32 v[46:47], v[46:47], v[50:51]
	v_pk_add_f32 v[48:49], v[40:41], v[48:49]
	v_cvt_pk_bf16_f32 v40, v44, v45
	v_mul_f32_e32 v45, v45, v45
	v_fmac_f32_e32 v45, v44, v44
	v_mul_f32_e32 v44, v47, v47
	v_fmac_f32_e32 v44, v46, v46
	v_lshlrev_b32_e32 v50, 16, v71
	v_and_b32_e32 v51, 0xffff0000, v71
	v_add_f32_e32 v44, v45, v44
	v_mul_f32_e32 v45, v49, v49
	v_pk_add_f32 v[50:51], v[42:43], v[50:51]
	v_fmac_f32_e32 v45, v48, v48
	v_add_f32_e32 v44, v45, v44
	v_mul_f32_e32 v45, v51, v51
	v_fmac_f32_e32 v45, v50, v50
	v_cvt_pk_bf16_f32 v41, v46, v47
	v_cvt_pk_bf16_f32 v42, v48, v49
	v_add_f32_e32 v48, v45, v44
	s_waitcnt vmcnt(2)
	v_lshlrev_b32_e32 v44, 16, v64
	v_and_b32_e32 v45, 0xffff0000, v64
	v_lshlrev_b32_e32 v46, 16, v65
	v_and_b32_e32 v47, 0xffff0000, v65
	v_pk_add_f32 v[38:39], v[38:39], v[46:47]
	v_pk_add_f32 v[36:37], v[36:37], v[44:45]
	v_lshlrev_b32_e32 v44, 16, v66
	v_and_b32_e32 v45, 0xffff0000, v66
	v_lshlrev_b32_e32 v46, 16, v67
	v_and_b32_e32 v47, 0xffff0000, v67
	v_pk_add_f32 v[46:47], v[34:35], v[46:47]
	v_pk_add_f32 v[44:45], v[32:33], v[44:45]
	v_mul_f32_e32 v34, v37, v37
	v_mul_f32_e32 v35, v39, v39
	v_mul_f32_e32 v33, v45, v45
	v_fmac_f32_e32 v34, v36, v36
	v_fmac_f32_e32 v35, v38, v38
	v_mul_f32_e32 v32, v47, v47
	v_fmac_f32_e32 v33, v44, v44
	v_add_f32_e32 v34, v34, v35
	v_fmac_f32_e32 v32, v46, v46
	v_add_f32_e32 v33, v33, v34
	v_add_f32_e32 v32, v32, v33
	v_add_f32_e32 v35, v48, v32
	v_cvt_pk_bf16_f32 v43, v50, v51
	ds_bpermute_b32 v50, v112, v35
	v_lshl_add_u64 v[32:33], s[96:97], 0, v[74:75]
	v_lshl_add_u64 v[48:49], v[152:153], 1, v[32:33]
	global_store_dwordx4 v[48:49], v[40:43], off sc1
	v_cvt_pk_bf16_f32 v34, v36, v37
	s_waitcnt lgkmcnt(0)
	v_add_f32_e32 v32, v35, v50
	ds_bpermute_b32 v33, v113, v32
	v_cvt_pk_bf16_f32 v35, v38, v39
	v_cvt_pk_bf16_f32 v36, v44, v45
	v_cvt_pk_bf16_f32 v37, v46, v47
	global_store_dwordx4 v[48:49], v[34:37], off offset:256 sc1
	s_and_saveexec_b64 s[0:1], vcc
	s_cbranch_execz .LBB0_1116
	s_waitcnt lgkmcnt(0)
	v_add_f32_e32 v34, v32, v33
	v_lshl_add_u64 v[32:33], v[72:73], 2, s[10:11]
	global_atomic_add_f32 v[32:33], v34, off
; __device__ __forceinline__ unsigned cvt_pk_bf16(float lo, float hi) { unsigned r; asm volatile("v_cvt_pk_bf16_f32 %0, %1, %2" : "=v"(r) : "v"(lo), "v"(hi)); return r; }
;     __device__ __forceinline__ void row_out(const f32x4 v0, const f32x4 v1, int row, int col, float& ss) const {
;         if (C) { float* rowp = C + (size_t)row * ldc + col; __builtin_nontemporal_store(v0, (f32x4*)rowp); __builtin_nontemporal_store(v1, (f32x4*)(rowp + 4)); }
;         if (wxb) { u32x4 w; w.x = cvt_pk_bf16(v0[0], v0[1]); w.y = cvt_pk_bf16(v0[2], v0[3]); w.z = cvt_pk_bf16(v1[0], v1[1]); w.w = cvt_pk_bf16(v1[2], v1[3]);
;             *(u32x4*)(XB0 + (size_t)row * ldc + col) = w;
;             ss += (v0[0] * v0[0] + v0[1] * v0[1]) + (v0[2] * v0[2] + v0[3] * v0[3]) + (v1[0] * v1[0] + v1[1] * v1[1]) + (v1[2] * v1[2] + v1[3] * v1[3]); }
;     }
;     __device__ __forceinline__ void operator()(const f32x4 (&acc)[2][2][4][2], const Unit& u, int wr, int wc, int fr, int fq) const {
;     ...
;               for (int mh = 0; mh < 4; mh += 2) {
;                 u32x4 rw[2][2];
; #pragma unroll
;                 for (int mm = 0; mm < 2; ++mm) { const int row = row0 + ai * HALF + (mh + mm) * 16;
; #pragma unroll
;                     for (int bj = 0; bj < 2; ++bj) if (bj == 0 || !u.q) rw[mm][bj] = *(const u32x4*)(XB0 + (size_t)row * ldc + col0 + bj * HALF); }
; #pragma unroll
;                 for (int mm = 0; mm < 2; ++mm) { const int m = mh + mm, row = row0 + ai * HALF + m * 16; float ss = 0.f;
; #pragma unroll
;                     for (int bj = 0; bj < 2; ++bj) if (bj == 0 || !u.q) { const u32x4 w = rw[mm][bj];
;                         const f32x4 v0 = acc[ai][bj][m][0] + (f32x4){bf_lo(w.x), bf_hi(w.x), bf_lo(w.y), bf_hi(w.y)}, v1 = acc[ai][bj][m][1] + (f32x4){bf_lo(w.z), bf_hi(w.z), bf_lo(w.w), bf_hi(w.w)};
;                         row_out(v0, v1, row, col0 + bj * HALF, ss); }
;                     if (wxb) { ss += __shfl_xor(ss, 16); ss += __shfl_xor(ss, 32); if (fq == 0) unsafeAtomicAdd(SS + row, ss); } }
.LBB0_1116:
	s_or_b64 exec, exec, s[0:1]
	v_add_u32_e32 v44, 0xa0, v154
	v_ashrrev_i32_e32 v45, 31, v44
	v_lshlrev_b64 v[54:55], 11, v[44:45]
	s_waitcnt lgkmcnt(0)
	v_lshl_add_u64 v[32:33], v[156:157], 0, v[54:55]
	global_load_dwordx4 v[46:49], v[32:33], off
	global_load_dwordx4 v[50:53], v[32:33], off offset:256
	v_add_u32_e32 v40, 0xb0, v154
	v_ashrrev_i32_e32 v41, 31, v40
	v_lshlrev_b64 v[42:43], 11, v[40:41]
	v_lshl_add_u64 v[32:33], v[156:157], 0, v[42:43]
	global_load_dwordx4 v[36:39], v[32:33], off
	s_nop 0
	global_load_dwordx4 v[32:35], v[32:33], off offset:256
	v_lshl_add_u64 v[54:55], s[96:97], 0, v[54:55]
	v_lshl_add_u64 v[54:55], v[152:153], 1, v[54:55]
	s_waitcnt vmcnt(3)
	v_lshlrev_b32_e32 v56, 16, v46
	v_and_b32_e32 v57, 0xffff0000, v46
	v_lshlrev_b32_e32 v46, 16, v47
	v_and_b32_e32 v47, 0xffff0000, v47
	v_pk_add_f32 v[30:31], v[30:31], v[46:47]
	v_lshlrev_b32_e32 v46, 16, v48
	v_and_b32_e32 v47, 0xffff0000, v48
	v_pk_add_f32 v[28:29], v[28:29], v[56:57]
	v_lshlrev_b32_e32 v48, 16, v49
	v_and_b32_e32 v49, 0xffff0000, v49
	v_pk_add_f32 v[46:47], v[24:25], v[46:47]
	v_cvt_pk_bf16_f32 v24, v28, v29
	v_cvt_pk_bf16_f32 v25, v30, v31
	v_pk_add_f32 v[48:49], v[26:27], v[48:49]
	v_cvt_pk_bf16_f32 v26, v46, v47
	s_nop 0
	v_cvt_pk_bf16_f32 v27, v48, v49
	global_store_dwordx4 v[54:55], v[24:27], off sc1
	s_nop 1
	v_mul_f32_e32 v24, v29, v29
	v_mul_f32_e32 v25, v31, v31
	v_fmac_f32_e32 v24, v28, v28
	v_fmac_f32_e32 v25, v30, v30
	v_add_f32_e32 v24, v24, v25
	v_mul_f32_e32 v25, v47, v47
	v_fmac_f32_e32 v25, v46, v46
	v_add_f32_e32 v24, v25, v24
	v_mul_f32_e32 v25, v49, v49
	v_fmac_f32_e32 v25, v48, v48
	v_add_f32_e32 v28, v25, v24
	s_waitcnt vmcnt(3)
	v_lshlrev_b32_e32 v24, 16, v50
	v_and_b32_e32 v25, 0xffff0000, v50
	v_lshlrev_b32_e32 v26, 16, v51
	v_and_b32_e32 v27, 0xffff0000, v51
	v_pk_add_f32 v[22:23], v[22:23], v[26:27]
	v_pk_add_f32 v[20:21], v[20:21], v[24:25]
	v_lshlrev_b32_e32 v24, 16, v52
	v_and_b32_e32 v25, 0xffff0000, v52
	v_lshlrev_b32_e32 v26, 16, v53
	v_and_b32_e32 v27, 0xffff0000, v53
	v_pk_add_f32 v[26:27], v[18:19], v[26:27]
	v_pk_add_f32 v[24:25], v[16:17], v[24:25]
	v_cvt_pk_bf16_f32 v16, v20, v21
	v_cvt_pk_bf16_f32 v17, v22, v23
	s_nop 0
	v_cvt_pk_bf16_f32 v18, v24, v25
	v_cvt_pk_bf16_f32 v19, v26, v27
	global_store_dwordx4 v[54:55], v[16:19], off offset:256 sc1
	s_nop 1
	v_mul_f32_e32 v18, v21, v21
	v_mul_f32_e32 v19, v23, v23
	v_mul_f32_e32 v17, v25, v25
	v_fmac_f32_e32 v18, v20, v20
	v_fmac_f32_e32 v19, v22, v22
	v_mul_f32_e32 v16, v27, v27
	v_fmac_f32_e32 v17, v24, v24
	v_add_f32_e32 v18, v18, v19
	v_fmac_f32_e32 v16, v26, v26
	v_add_f32_e32 v17, v17, v18
	v_add_f32_e32 v16, v16, v17
	v_add_f32_e32 v16, v28, v16
	ds_bpermute_b32 v17, v112, v16
	s_waitcnt lgkmcnt(0)
	v_add_f32_e32 v16, v16, v17
	ds_bpermute_b32 v17, v113, v16
	s_and_saveexec_b64 s[0:1], vcc
	s_cbranch_execz .LBB0_1118
	s_waitcnt lgkmcnt(0)
	v_add_f32_e32 v18, v16, v17
	v_lshl_add_u64 v[16:17], v[44:45], 2, s[10:11]
	global_atomic_add_f32 v[16:17], v18, off
.LBB0_1118:
	s_or_b64 exec, exec, s[0:1]
	s_waitcnt vmcnt(3)
	v_lshlrev_b32_e32 v16, 16, v36
	s_waitcnt lgkmcnt(0)
	v_and_b32_e32 v17, 0xffff0000, v36
	v_lshlrev_b32_e32 v18, 16, v37
	v_and_b32_e32 v19, 0xffff0000, v37
	v_pk_add_f32 v[12:13], v[12:13], v[16:17]
	v_lshlrev_b32_e32 v16, 16, v38
	v_and_b32_e32 v17, 0xffff0000, v38
	v_pk_add_f32 v[14:15], v[14:15], v[18:19]
	v_pk_add_f32 v[16:17], v[8:9], v[16:17]
	v_cvt_pk_bf16_f32 v8, v12, v13
	v_mul_f32_e32 v13, v13, v13
	v_fmac_f32_e32 v13, v12, v12
	v_mul_f32_e32 v12, v15, v15
	v_fmac_f32_e32 v12, v14, v14
	v_lshlrev_b32_e32 v18, 16, v39
	v_and_b32_e32 v19, 0xffff0000, v39
	v_add_f32_e32 v12, v13, v12
	v_mul_f32_e32 v13, v17, v17
	v_pk_add_f32 v[18:19], v[10:11], v[18:19]
	v_fmac_f32_e32 v13, v16, v16
	v_add_f32_e32 v12, v13, v12
	v_mul_f32_e32 v13, v19, v19
	v_fmac_f32_e32 v13, v18, v18
	v_cvt_pk_bf16_f32 v9, v14, v15
	v_cvt_pk_bf16_f32 v10, v16, v17
	v_add_f32_e32 v16, v13, v12
	s_waitcnt vmcnt(2)
	v_lshlrev_b32_e32 v12, 16, v32
	v_and_b32_e32 v13, 0xffff0000, v32
	v_lshlrev_b32_e32 v14, 16, v33
	v_and_b32_e32 v15, 0xffff0000, v33
	v_pk_add_f32 v[6:7], v[6:7], v[14:15]
	v_pk_add_f32 v[4:5], v[4:5], v[12:13]
	v_lshlrev_b32_e32 v12, 16, v34
	v_and_b32_e32 v13, 0xffff0000, v34
	v_lshlrev_b32_e32 v14, 16, v35
	v_and_b32_e32 v15, 0xffff0000, v35
	v_pk_add_f32 v[14:15], v[2:3], v[14:15]
	v_pk_add_f32 v[12:13], v[0:1], v[12:13]
	v_mul_f32_e32 v2, v5, v5
	v_mul_f32_e32 v3, v7, v7
	v_mul_f32_e32 v1, v13, v13
	v_fmac_f32_e32 v2, v4, v4
	v_fmac_f32_e32 v3, v6, v6
	v_mul_f32_e32 v0, v15, v15
	v_fmac_f32_e32 v1, v12, v12
	v_add_f32_e32 v2, v2, v3
	v_fmac_f32_e32 v0, v14, v14
	v_add_f32_e32 v1, v1, v2
	v_add_f32_e32 v0, v0, v1
	v_add_f32_e32 v3, v16, v0
	v_cvt_pk_bf16_f32 v11, v18, v19
	ds_bpermute_b32 v18, v112, v3
	v_lshl_add_u64 v[0:1], s[96:97], 0, v[42:43]
	v_lshl_add_u64 v[16:17], v[152:153], 1, v[0:1]
	global_store_dwordx4 v[16:17], v[8:11], off sc1
	v_cvt_pk_bf16_f32 v2, v4, v5
	s_waitcnt lgkmcnt(0)
	v_add_f32_e32 v0, v3, v18
	ds_bpermute_b32 v1, v113, v0
	v_cvt_pk_bf16_f32 v3, v6, v7
	v_cvt_pk_bf16_f32 v4, v12, v13
	v_cvt_pk_bf16_f32 v5, v14, v15
	global_store_dwordx4 v[16:17], v[2:5], off offset:256 sc1
	s_and_saveexec_b64 s[0:1], vcc
	s_cbranch_execz .LBB0_1120
	v_lshl_add_u64 v[2:3], v[40:41], 2, s[10:11]
	s_waitcnt lgkmcnt(0)
	v_add_f32_e32 v0, v0, v1
	global_atomic_add_f32 v[2:3], v0, off

;     __device__ __forceinline__ void operator()(const f32x4 (&acc)[2][2][4][2], const Unit& u, int wr, int wc, int fr, int fq) const {
;     ...
;         const int row0 = u.rb + wr * 64 + fr;
;         float rs[2][4];
; #pragma unroll
;         for (int ai = 0; ai < 2; ++ai) if (ai == 0 || !u.half)
; #pragma unroll
;             for (int m = 0; m < 4; ++m) rs[ai][m] = rsqrtf(SS[row0 + (u.half ? 0 : ai * HALF) + m * 16] * (1.f / 1024.f) + 1e-6f);
;     ...
;         } else {
;             const int col0 = (u.cb - 1024) + wc * 32 + 8 * fq;
; #pragma unroll
;             for (int ai = 0; ai < 2; ++ai) if (ai == 0 || !u.half)
; #pragma unroll
;                 for (int m = 0; m < 4; ++m) { float* rowp = KV + (size_t)(row0 + ai * HALF + m * 16) * 512 + col0;
; #pragma unroll
;                     for (int bj = 0; bj < 2; ++bj) if (bj == 0 || !u.q) { *(f32x4*)(rowp + bj * HALF) = acc[ai][bj][m][0] * rs[ai][m]; *(f32x4*)(rowp + bj * HALF + 4) = acc[ai][bj][m][1] * rs[ai][m]; } }
.LBB0_1211:
	v_mov_b32_e32 v128, v157
	v_mov_b32_e32 v130, v159
	s_add_i32 s2, s44, s55
	s_cmp_gt_i32 s45, 3
	v_add_u32_e32 v170, s2, v128
	v_ashrrev_i32_e32 v171, 31, v170
	v_lshl_add_u64 v[128:129], v[170:171], 2, s[10:11]
	global_load_dword v131, v[128:129], off
	v_lshlrev_b32_e32 v176, 3, v130
	v_lshlrev_b64 v[174:175], 11, v[170:171]
	s_mov_b64 s[44:45], -1
	s_waitcnt vmcnt(0)
	v_fmamk_f32 v131, v131, 0x3a800000, v169
	v_cmp_gt_f32_e32 vcc, s86, v131
	v_mul_f32_e32 v132, 0x4b800000, v131
	s_nop 0
	v_cndmask_b32_e32 v131, v131, v132, vcc
	v_rsq_f32_e32 v131, v131
	s_nop 0
	v_mul_f32_e32 v132, 0x45800000, v131
	v_cndmask_b32_e32 v172, v131, v132, vcc
	global_load_dword v131, v[128:129], off offset:64
	v_mov_b32_e32 v173, v172
	v_pk_mul_f32 v[126:127], v[126:127], v[172:173] op_sel_hi:[1,0]
	v_pk_mul_f32 v[124:125], v[124:125], v[172:173] op_sel_hi:[1,0]
	v_pk_mul_f32 v[136:137], v[120:121], v[172:173]
	s_waitcnt vmcnt(0)
	v_fmamk_f32 v131, v131, 0x3a800000, v169
	v_cmp_gt_f32_e32 vcc, s86, v131
	v_mul_f32_e32 v132, 0x4b800000, v131
	s_nop 0
	v_cndmask_b32_e32 v131, v131, v132, vcc
	v_rsq_f32_e32 v131, v131
	s_nop 0
	v_mul_f32_e32 v132, 0x45800000, v131
	v_cndmask_b32_e32 v168, v131, v132, vcc
	global_load_dword v131, v[128:129], off offset:128
	s_waitcnt vmcnt(0)
	v_fmamk_f32 v131, v131, 0x3a800000, v169
	v_cmp_gt_f32_e32 vcc, s86, v131
	v_mul_f32_e32 v132, 0x4b800000, v131
	s_nop 0
	v_cndmask_b32_e32 v131, v131, v132, vcc
	v_rsq_f32_e32 v131, v131
	s_nop 0
	v_mul_f32_e32 v132, 0x45800000, v131
	v_cndmask_b32_e32 v166, v131, v132, vcc
	global_load_dword v131, v[128:129], off offset:192
	s_waitcnt vmcnt(0)
	v_fmamk_f32 v131, v131, 0x3a800000, v169
	v_cmp_gt_f32_e32 vcc, s86, v131
	v_mul_f32_e32 v132, 0x4b800000, v131
	s_nop 0
	v_cndmask_b32_e32 v131, v131, v132, vcc
	v_rsq_f32_e32 v131, v131
	s_nop 0
	v_mul_f32_e32 v132, 0x45800000, v131
	v_cndmask_b32_e32 v164, v131, v132, vcc
	global_load_dword v131, v[128:129], off offset:512
	s_waitcnt vmcnt(0)
	v_fmamk_f32 v131, v131, 0x3a800000, v169
	v_cmp_gt_f32_e32 vcc, s86, v131
	v_mul_f32_e32 v132, 0x4b800000, v131
	s_nop 0
	v_cndmask_b32_e32 v131, v131, v132, vcc
	v_rsq_f32_e32 v131, v131
	s_nop 0
	v_mul_f32_e32 v132, 0x45800000, v131
	v_cndmask_b32_e32 v162, v131, v132, vcc
	global_load_dword v131, v[128:129], off offset:576
	s_waitcnt vmcnt(0)
	v_fmamk_f32 v131, v131, 0x3a800000, v169
	v_cmp_gt_f32_e32 vcc, s86, v131
	v_mul_f32_e32 v132, 0x4b800000, v131
	s_nop 0
	v_cndmask_b32_e32 v131, v131, v132, vcc
	v_rsq_f32_e32 v131, v131
	s_nop 0
	v_mul_f32_e32 v132, 0x45800000, v131
	v_cndmask_b32_e32 v160, v131, v132, vcc
	global_load_dword v131, v[128:129], off offset:640
	s_waitcnt vmcnt(0)
	v_fmamk_f32 v131, v131, 0x3a800000, v169
	global_load_dword v128, v[128:129], off offset:704
	v_cmp_gt_f32_e32 vcc, s86, v131
	v_mul_f32_e32 v132, 0x4b800000, v131
	s_waitcnt vmcnt(0)
	v_fmamk_f32 v128, v128, 0x3a800000, v169
	v_cndmask_b32_e32 v131, v131, v132, vcc
	v_rsq_f32_e32 v131, v131
	v_mul_f32_e32 v129, 0x4b800000, v128
	v_mul_f32_e32 v132, 0x45800000, v131
	v_cndmask_b32_e32 v158, v131, v132, vcc
	v_cmp_gt_f32_e32 vcc, s86, v128
	v_pk_mul_f32 v[132:133], v[116:117], v[172:173]
	s_nop 0
	v_cndmask_b32_e32 v128, v128, v129, vcc
	v_rsq_f32_e32 v128, v128
	s_nop 0
	v_mul_f32_e32 v129, 0x45800000, v128
	v_cndmask_b32_e32 v156, v128, v129, vcc
	v_pk_mul_f32 v[128:129], v[112:113], v[172:173]
	s_cbranch_scc0 .LBB0_1214
	s_add_i32 s2, s71, s1
	v_add_u32_e32 v112, s2, v176
	v_readlane_b32 s2, v240, 58
	v_ashrrev_i32_e32 v113, 31, v112
	v_readlane_b32 s3, v240, 59
	v_lshlrev_b64 v[112:113], 2, v[112:113]
	v_pk_mul_f32 v[180:181], v[110:111], v[168:169] op_sel_hi:[1,0]
	v_lshl_add_u64 v[116:117], s[2:3], 0, v[174:175]
	v_lshl_add_u64 v[112:113], v[116:117], 0, v[112:113]
	v_add_co_u32_e32 v120, vcc, s73, v112
	s_mov_b64 s[2:3], 0x8000
	v_pk_mul_f32 v[178:179], v[108:109], v[168:169] op_sel_hi:[1,0]
	v_addc_co_u32_e32 v121, vcc, 0, v113, vcc
	v_lshl_add_u64 v[116:117], v[112:113], 0, s[2:3]
	global_store_dwordx4 v[120:121], v[178:181], off sc1
	v_add_co_u32_e32 v120, vcc, s59, v112
	s_nop 0
	v_pk_mul_f32 v[180:181], v[106:107], v[168:169] op_sel_hi:[1,0]
	v_pk_mul_f32 v[178:179], v[104:105], v[168:169] op_sel_hi:[1,0]
	global_store_dwordx4 v[116:117], v[178:181], off offset:16 sc1
	v_addc_co_u32_e32 v121, vcc, 0, v113, vcc
	s_nop 0
	v_pk_mul_f32 v[180:181], v[102:103], v[168:169] op_sel_hi:[1,0]
	v_pk_mul_f32 v[178:179], v[100:101], v[168:169] op_sel_hi:[1,0]
	global_store_dwordx4 v[116:117], v[178:181], off offset:512 sc1
	v_mov_b32_e32 v173, v172
	v_pk_mul_f32 v[138:139], v[122:123], v[172:173]
	v_pk_mul_f32 v[180:181], v[94:95], v[168:169] op_sel_hi:[1,0]
	v_pk_mul_f32 v[178:179], v[92:93], v[168:169] op_sel_hi:[1,0]
	global_store_dwordx4 v[116:117], v[178:181], off offset:528 sc1
	v_lshl_add_u64 v[116:117], v[112:113], 0, s[18:19]
	v_pk_mul_f32 v[134:135], v[118:119], v[172:173]
	v_pk_mul_f32 v[180:181], v[98:99], v[166:167] op_sel_hi:[1,0]
	v_pk_mul_f32 v[178:179], v[96:97], v[166:167] op_sel_hi:[1,0]
	global_store_dwordx4 v[120:121], v[178:181], off sc1
	v_add_co_u32_e32 v120, vcc, s72, v112
	s_nop 0
	v_pk_mul_f32 v[180:181], v[90:91], v[166:167] op_sel_hi:[1,0]
	v_pk_mul_f32 v[178:179], v[88:89], v[166:167] op_sel_hi:[1,0]
;     __device__ __forceinline__ void operator()(const f32x4 (&acc)[2][2][4][2], const Unit& u, int wr, int wc, int fr, int fq) const {
;     ...
;         } else {
;             const int col0 = (u.cb - 1024) + wc * 32 + 8 * fq;
; #pragma unroll
;             for (int ai = 0; ai < 2; ++ai) if (ai == 0 || !u.half)
; #pragma unroll
;                 for (int m = 0; m < 4; ++m) { float* rowp = KV + (size_t)(row0 + ai * HALF + m * 16) * 512 + col0;
; #pragma unroll
;                     for (int bj = 0; bj < 2; ++bj) if (bj == 0 || !u.q) { *(f32x4*)(rowp + bj * HALF) = acc[ai][bj][m][0] * rs[ai][m]; *(f32x4*)(rowp + bj * HALF + 4) = acc[ai][bj][m][1] * rs[ai][m]; } }
	global_store_dwordx4 v[116:117], v[178:181], off offset:16 sc1
	v_addc_co_u32_e32 v121, vcc, 0, v113, vcc
	s_nop 0
	v_pk_mul_f32 v[180:181], v[86:87], v[166:167] op_sel_hi:[1,0]
	v_pk_mul_f32 v[178:179], v[84:85], v[166:167] op_sel_hi:[1,0]
	global_store_dwordx4 v[116:117], v[178:181], off offset:512 sc1
	v_pk_mul_f32 v[130:131], v[114:115], v[172:173]
	global_store_dwordx4 v[112:113], v[124:127], off sc1
	v_pk_mul_f32 v[180:181], v[78:79], v[166:167] op_sel_hi:[1,0]
	v_pk_mul_f32 v[178:179], v[76:77], v[166:167] op_sel_hi:[1,0]
	global_store_dwordx4 v[116:117], v[178:181], off offset:528 sc1
	v_lshl_add_u64 v[116:117], v[112:113], 0, s[20:21]
	global_store_dwordx4 v[112:113], v[136:139], off offset:16 sc1
	v_pk_mul_f32 v[180:181], v[82:83], v[164:165] op_sel_hi:[1,0]
	v_pk_mul_f32 v[178:179], v[80:81], v[164:165] op_sel_hi:[1,0]
	global_store_dwordx4 v[120:121], v[178:181], off sc1
	v_add_co_u32_e32 v120, vcc, s87, v112
	s_nop 0
	v_pk_mul_f32 v[180:181], v[74:75], v[164:165] op_sel_hi:[1,0]
	v_pk_mul_f32 v[178:179], v[72:73], v[164:165] op_sel_hi:[1,0]
	global_store_dwordx4 v[116:117], v[178:181], off offset:16 sc1
	v_addc_co_u32_e32 v121, vcc, 0, v113, vcc
	s_nop 0
	v_pk_mul_f32 v[180:181], v[70:71], v[164:165] op_sel_hi:[1,0]
	v_pk_mul_f32 v[178:179], v[68:69], v[164:165] op_sel_hi:[1,0]
	global_store_dwordx4 v[116:117], v[178:181], off offset:512 sc1
	global_store_dwordx4 v[112:113], v[132:135], off offset:512 sc1
	global_store_dwordx4 v[112:113], v[128:131], off offset:528 sc1
	v_pk_mul_f32 v[180:181], v[66:67], v[164:165] op_sel_hi:[1,0]
	v_pk_mul_f32 v[178:179], v[64:65], v[164:165] op_sel_hi:[1,0]
	global_store_dwordx4 v[116:117], v[178:181], off offset:528 sc1
	v_lshl_add_u64 v[116:117], v[112:113], 0, s[60:61]
	s_nop 0
	v_pk_mul_f32 v[180:181], v[62:63], v[162:163] op_sel_hi:[1,0]
	v_pk_mul_f32 v[178:179], v[60:61], v[162:163] op_sel_hi:[1,0]
	global_store_dwordx4 v[120:121], v[178:181], off sc1
	v_add_co_u32_e32 v120, vcc, s91, v112
	s_nop 0
	v_pk_mul_f32 v[180:181], v[58:59], v[162:163] op_sel_hi:[1,0]
	v_pk_mul_f32 v[178:179], v[56:57], v[162:163] op_sel_hi:[1,0]
	global_store_dwordx4 v[116:117], v[178:181], off offset:16 sc1
	v_addc_co_u32_e32 v121, vcc, 0, v113, vcc
	s_nop 0
	v_pk_mul_f32 v[180:181], v[54:55], v[162:163] op_sel_hi:[1,0]
	v_pk_mul_f32 v[178:179], v[52:53], v[162:163] op_sel_hi:[1,0]
	global_store_dwordx4 v[116:117], v[178:181], off offset:512 sc1
	s_nop 1
	v_pk_mul_f32 v[180:181], v[46:47], v[162:163] op_sel_hi:[1,0]
	v_pk_mul_f32 v[178:179], v[44:45], v[162:163] op_sel_hi:[1,0]
	global_store_dwordx4 v[116:117], v[178:181], off offset:528 sc1
	v_lshl_add_u64 v[116:117], v[112:113], 0, s[28:29]
	s_nop 0
	v_pk_mul_f32 v[180:181], v[50:51], v[160:161] op_sel_hi:[1,0]
	v_pk_mul_f32 v[178:179], v[48:49], v[160:161] op_sel_hi:[1,0]
	global_store_dwordx4 v[120:121], v[178:181], off sc1
	v_add_co_u32_e32 v120, vcc, s5, v112
	s_nop 0
	v_pk_mul_f32 v[180:181], v[42:43], v[160:161] op_sel_hi:[1,0]
	v_pk_mul_f32 v[178:179], v[40:41], v[160:161] op_sel_hi:[1,0]
	global_store_dwordx4 v[116:117], v[178:181], off offset:16 sc1
	v_addc_co_u32_e32 v121, vcc, 0, v113, vcc
	s_nop 0
	v_pk_mul_f32 v[180:181], v[38:39], v[160:161] op_sel_hi:[1,0]
	v_pk_mul_f32 v[178:179], v[36:37], v[160:161] op_sel_hi:[1,0]
	global_store_dwordx4 v[116:117], v[178:181], off offset:512 sc1
	s_nop 1
	v_pk_mul_f32 v[180:181], v[30:31], v[160:161] op_sel_hi:[1,0]
	v_pk_mul_f32 v[178:179], v[28:29], v[160:161] op_sel_hi:[1,0]
	global_store_dwordx4 v[116:117], v[178:181], off offset:528 sc1
	v_lshl_add_u64 v[116:117], v[112:113], 0, s[30:31]
	s_nop 0
	v_pk_mul_f32 v[180:181], v[34:35], v[158:159] op_sel_hi:[1,0]
	v_pk_mul_f32 v[178:179], v[32:33], v[158:159] op_sel_hi:[1,0]
	global_store_dwordx4 v[120:121], v[178:181], off sc1
	s_nop 1
	v_pk_mul_f32 v[180:181], v[26:27], v[158:159] op_sel_hi:[1,0]
	v_pk_mul_f32 v[178:179], v[24:25], v[158:159] op_sel_hi:[1,0]
	global_store_dwordx4 v[116:117], v[178:181], off offset:16 sc1
	s_nop 1
	v_pk_mul_f32 v[180:181], v[22:23], v[158:159] op_sel_hi:[1,0]
	v_pk_mul_f32 v[178:179], v[20:21], v[158:159] op_sel_hi:[1,0]
	global_store_dwordx4 v[116:117], v[178:181], off offset:512 sc1
	s_nop 1
	v_pk_mul_f32 v[180:181], v[14:15], v[158:159] op_sel_hi:[1,0]
	v_pk_mul_f32 v[178:179], v[12:13], v[158:159] op_sel_hi:[1,0]
	global_store_dwordx4 v[116:117], v[178:181], off offset:528 sc1
	v_lshl_add_u64 v[116:117], v[112:113], 0, s[34:35]
	v_add_co_u32_e32 v112, vcc, s54, v112
	v_pk_mul_f32 v[180:181], v[18:19], v[156:157] op_sel_hi:[1,0]
	v_pk_mul_f32 v[178:179], v[16:17], v[156:157] op_sel_hi:[1,0]
	v_addc_co_u32_e32 v113, vcc, 0, v113, vcc
	global_store_dwordx4 v[112:113], v[178:181], off sc1
	s_nop 1
	v_pk_mul_f32 v[180:181], v[10:11], v[156:157] op_sel_hi:[1,0]
	v_pk_mul_f32 v[178:179], v[8:9], v[156:157] op_sel_hi:[1,0]
	global_store_dwordx4 v[116:117], v[178:181], off offset:16 sc1
	s_nop 1
	v_pk_mul_f32 v[180:181], v[6:7], v[156:157] op_sel_hi:[1,0]
	v_pk_mul_f32 v[178:179], v[4:5], v[156:157] op_sel_hi:[1,0]
	global_store_dwordx4 v[116:117], v[178:181], off offset:512 sc1
	s_nop 1
	v_pk_mul_f32 v[180:181], v[2:3], v[156:157] op_sel_hi:[1,0]
	v_pk_mul_f32 v[178:179], v[0:1], v[156:157] op_sel_hi:[1,0]
	global_store_dwordx4 v[116:117], v[178:181], off offset:528 sc1
	s_cbranch_execz .LBB0_1215

; __device__ __forceinline__ unsigned cvt_pk_bf16(float lo, float hi) { unsigned r; asm volatile("v_cvt_pk_bf16_f32 %0, %1, %2" : "=v"(r) : "v"(lo), "v"(hi)); return r; }
;     __device__ __forceinline__ void operator()(const f32x4 (&acc)[2][2][4][2], const Unit& u, int wr, int wc, int fr, int fq) const {
;     ...
;         if (u.pn < 4) {
;             const int col0 = u.cb + wc * 32 + 8 * fq;
; #pragma unroll
;             for (int ai = 0; ai < 2; ++ai) if (ai == 0 || !u.half)
; #pragma unroll
;                 for (int m = 0; m < 4; ++m) { bf16_t* rowp = Q + (size_t)(row0 + ai * HALF + m * 16) * 1024 + col0;
; #pragma unroll
;                     for (int bj = 0; bj < 2; ++bj) if (bj == 0 || !u.q) { const f32x4 v0 = acc[ai][bj][m][0] * rs[ai][m], v1 = acc[ai][bj][m][1] * rs[ai][m];
;                         u32x4 w; w.x = cvt_pk_bf16(v0[0], v0[1]); w.y = cvt_pk_bf16(v0[2], v0[3]); w.z = cvt_pk_bf16(v1[0], v1[1]); w.w = cvt_pk_bf16(v1[2], v1[3]);
;                         *(u32x4*)(rowp + bj * HALF) = w; } }
.LBB0_1215:
	s_add_i32 s1, s1, s56
	v_add_u32_e32 v112, s1, v176
	v_readlane_b32 s2, v240, 12
	v_ashrrev_i32_e32 v113, 31, v112
	v_readlane_b32 s3, v240, 13
	v_lshlrev_b64 v[130:131], 1, v[112:113]
	v_mov_b32_e32 v173, v172
	v_lshl_add_u64 v[116:117], s[2:3], 0, v[174:175]
	v_lshl_add_u64 v[116:117], v[116:117], 0, v[130:131]
	v_pk_mul_f32 v[112:113], v[122:123], v[172:173]
	v_cvt_pk_bf16_f32 v120, v124, v125
	v_cvt_pk_bf16_f32 v121, v126, v127
	v_cvt_pk_bf16_f32 v122, v136, v137
	v_pk_mul_f32 v[118:119], v[118:119], v[172:173]
	v_cvt_pk_bf16_f32 v123, v112, v113
	global_store_dwordx4 v[116:117], v[120:123], off sc1
	v_cvt_pk_bf16_f32 v112, v132, v133
	v_cvt_pk_bf16_f32 v113, v118, v119
	v_pk_mul_f32 v[108:109], v[108:109], v[168:169] op_sel_hi:[1,0]
	v_pk_mul_f32 v[110:111], v[110:111], v[168:169] op_sel_hi:[1,0]
	v_pk_mul_f32 v[120:121], v[114:115], v[172:173]
	v_cvt_pk_bf16_f32 v114, v128, v129
	v_pk_mul_f32 v[102:103], v[102:103], v[168:169] op_sel_hi:[1,0]
	v_cvt_pk_bf16_f32 v115, v120, v121
	global_store_dwordx4 v[116:117], v[112:115], off offset:256 sc1
	v_pk_mul_f32 v[116:117], v[106:107], v[168:169] op_sel_hi:[1,0]
	v_pk_mul_f32 v[106:107], v[104:105], v[168:169] op_sel_hi:[1,0]
	v_lshlrev_b64 v[112:113], 11, v[170:171]
	v_lshl_add_u64 v[112:113], s[2:3], 0, v[112:113]
	v_lshl_add_u64 v[112:113], v[112:113], 0, v[130:131]
	v_cvt_pk_bf16_f32 v104, v108, v109
	v_add_co_u32_e32 v108, vcc, s73, v112
	v_cvt_pk_bf16_f32 v105, v110, v111
	s_mov_b64 s[2:3], 0x8000
	s_nop 0
	v_addc_co_u32_e32 v109, vcc, 0, v113, vcc
	v_cvt_pk_bf16_f32 v106, v106, v107
	v_cvt_pk_bf16_f32 v107, v116, v117
	global_store_dwordx4 v[108:109], v[104:107], off sc1
	v_lshl_add_u64 v[114:115], v[112:113], 0, s[2:3]
	v_pk_mul_f32 v[100:101], v[100:101], v[168:169] op_sel_hi:[1,0]
	v_pk_mul_f32 v[104:105], v[94:95], v[168:169] op_sel_hi:[1,0]
	v_pk_mul_f32 v[94:95], v[92:93], v[168:169] op_sel_hi:[1,0]
	v_cvt_pk_bf16_f32 v92, v100, v101
	v_cvt_pk_bf16_f32 v93, v102, v103
	v_pk_mul_f32 v[96:97], v[96:97], v[166:167] op_sel_hi:[1,0]
	v_cvt_pk_bf16_f32 v94, v94, v95
	v_cvt_pk_bf16_f32 v95, v104, v105
	global_store_dwordx4 v[114:115], v[92:95], off offset:256 sc1
	v_pk_mul_f32 v[86:87], v[86:87], v[166:167] op_sel_hi:[1,0]
	v_pk_mul_f32 v[84:85], v[84:85], v[166:167] op_sel_hi:[1,0]
	v_pk_mul_f32 v[94:95], v[98:99], v[166:167] op_sel_hi:[1,0]
	v_pk_mul_f32 v[98:99], v[90:91], v[166:167] op_sel_hi:[1,0]
	v_pk_mul_f32 v[90:91], v[88:89], v[166:167] op_sel_hi:[1,0]
	v_cvt_pk_bf16_f32 v88, v96, v97
	v_cvt_pk_bf16_f32 v89, v94, v95
	v_add_co_u32_e32 v94, vcc, s59, v112
	v_cvt_pk_bf16_f32 v90, v90, v91
	v_cvt_pk_bf16_f32 v91, v98, v99
	v_lshl_add_u64 v[92:93], v[112:113], 0, s[18:19]
	s_nop 0
	v_addc_co_u32_e32 v95, vcc, 0, v113, vcc
	global_store_dwordx4 v[94:95], v[88:91], off sc1
	v_pk_mul_f32 v[80:81], v[80:81], v[164:165] op_sel_hi:[1,0]
	v_pk_mul_f32 v[70:71], v[70:71], v[164:165] op_sel_hi:[1,0]
	v_pk_mul_f32 v[88:89], v[78:79], v[166:167] op_sel_hi:[1,0]
	v_pk_mul_f32 v[78:79], v[76:77], v[166:167] op_sel_hi:[1,0]
	v_cvt_pk_bf16_f32 v76, v84, v85
	v_cvt_pk_bf16_f32 v77, v86, v87
	v_pk_mul_f32 v[68:69], v[68:69], v[164:165] op_sel_hi:[1,0]
	v_cvt_pk_bf16_f32 v78, v78, v79
	v_cvt_pk_bf16_f32 v79, v88, v89
	global_store_dwordx4 v[92:93], v[76:79], off offset:256 sc1
	v_pk_mul_f32 v[60:61], v[60:61], v[162:163] op_sel_hi:[1,0]
	v_pk_mul_f32 v[62:63], v[62:63], v[162:163] op_sel_hi:[1,0]
	v_pk_mul_f32 v[78:79], v[82:83], v[164:165] op_sel_hi:[1,0]
	v_pk_mul_f32 v[82:83], v[74:75], v[164:165] op_sel_hi:[1,0]
	v_pk_mul_f32 v[74:75], v[72:73], v[164:165] op_sel_hi:[1,0]
	v_cvt_pk_bf16_f32 v72, v80, v81
	v_cvt_pk_bf16_f32 v73, v78, v79
	v_add_co_u32_e32 v78, vcc, s72, v112
	v_cvt_pk_bf16_f32 v74, v74, v75
	v_cvt_pk_bf16_f32 v75, v82, v83
	v_lshl_add_u64 v[76:77], v[112:113], 0, s[20:21]
	s_nop 0
	v_addc_co_u32_e32 v79, vcc, 0, v113, vcc
	global_store_dwordx4 v[78:79], v[72:75], off sc1
	v_pk_mul_f32 v[54:55], v[54:55], v[162:163] op_sel_hi:[1,0]
	v_pk_mul_f32 v[52:53], v[52:53], v[162:163] op_sel_hi:[1,0]
	v_pk_mul_f32 v[72:73], v[66:67], v[164:165] op_sel_hi:[1,0]
; __device__ __forceinline__ unsigned cvt_pk_bf16(float lo, float hi) { unsigned r; asm volatile("v_cvt_pk_bf16_f32 %0, %1, %2" : "=v"(r) : "v"(lo), "v"(hi)); return r; }
;     __device__ __forceinline__ void operator()(const f32x4 (&acc)[2][2][4][2], const Unit& u, int wr, int wc, int fr, int fq) const {
;     ...
;         if (u.pn < 4) {
;             const int col0 = u.cb + wc * 32 + 8 * fq;
; #pragma unroll
;             for (int ai = 0; ai < 2; ++ai) if (ai == 0 || !u.half)
; #pragma unroll
;                 for (int m = 0; m < 4; ++m) { bf16_t* rowp = Q + (size_t)(row0 + ai * HALF + m * 16) * 1024 + col0;
; #pragma unroll
;                     for (int bj = 0; bj < 2; ++bj) if (bj == 0 || !u.q) { const f32x4 v0 = acc[ai][bj][m][0] * rs[ai][m], v1 = acc[ai][bj][m][1] * rs[ai][m];
;                         u32x4 w; w.x = cvt_pk_bf16(v0[0], v0[1]); w.y = cvt_pk_bf16(v0[2], v0[3]); w.z = cvt_pk_bf16(v1[0], v1[1]); w.w = cvt_pk_bf16(v1[2], v1[3]);
;                         *(u32x4*)(rowp + bj * HALF) = w; } }
	v_pk_mul_f32 v[66:67], v[64:65], v[164:165] op_sel_hi:[1,0]
	v_cvt_pk_bf16_f32 v64, v68, v69
	v_cvt_pk_bf16_f32 v65, v70, v71
	v_pk_mul_f32 v[48:49], v[48:49], v[160:161] op_sel_hi:[1,0]
	v_cvt_pk_bf16_f32 v66, v66, v67
	v_cvt_pk_bf16_f32 v67, v72, v73
	global_store_dwordx4 v[76:77], v[64:67], off offset:256 sc1
	v_pk_mul_f32 v[38:39], v[38:39], v[160:161] op_sel_hi:[1,0]
	v_pk_mul_f32 v[36:37], v[36:37], v[160:161] op_sel_hi:[1,0]
	v_pk_mul_f32 v[66:67], v[58:59], v[162:163] op_sel_hi:[1,0]
	v_pk_mul_f32 v[58:59], v[56:57], v[162:163] op_sel_hi:[1,0]
	v_cvt_pk_bf16_f32 v56, v60, v61
	v_add_co_u32_e32 v60, vcc, s87, v112
	v_cvt_pk_bf16_f32 v57, v62, v63
	v_cvt_pk_bf16_f32 v58, v58, v59
	v_cvt_pk_bf16_f32 v59, v66, v67
	v_lshl_add_u64 v[64:65], v[112:113], 0, s[60:61]
	s_nop 0
	v_addc_co_u32_e32 v61, vcc, 0, v113, vcc
	global_store_dwordx4 v[60:61], v[56:59], off sc1
	v_pk_mul_f32 v[32:33], v[32:33], v[158:159] op_sel_hi:[1,0]
	v_pk_mul_f32 v[22:23], v[22:23], v[158:159] op_sel_hi:[1,0]
	v_pk_mul_f32 v[56:57], v[46:47], v[162:163] op_sel_hi:[1,0]
	v_pk_mul_f32 v[46:47], v[44:45], v[162:163] op_sel_hi:[1,0]
	v_cvt_pk_bf16_f32 v44, v52, v53
	v_cvt_pk_bf16_f32 v45, v54, v55
	v_pk_mul_f32 v[20:21], v[20:21], v[158:159] op_sel_hi:[1,0]
	v_cvt_pk_bf16_f32 v46, v46, v47
	v_cvt_pk_bf16_f32 v47, v56, v57
	global_store_dwordx4 v[64:65], v[44:47], off offset:256 sc1
	v_pk_mul_f32 v[16:17], v[16:17], v[156:157] op_sel_hi:[1,0]
	v_pk_mul_f32 v[6:7], v[6:7], v[156:157] op_sel_hi:[1,0]
	v_pk_mul_f32 v[46:47], v[50:51], v[160:161] op_sel_hi:[1,0]
	v_pk_mul_f32 v[50:51], v[42:43], v[160:161] op_sel_hi:[1,0]
	v_pk_mul_f32 v[42:43], v[40:41], v[160:161] op_sel_hi:[1,0]
	v_cvt_pk_bf16_f32 v40, v48, v49
	v_cvt_pk_bf16_f32 v41, v46, v47
	v_add_co_u32_e32 v46, vcc, s91, v112
	v_cvt_pk_bf16_f32 v42, v42, v43
	v_cvt_pk_bf16_f32 v43, v50, v51
	v_lshl_add_u64 v[44:45], v[112:113], 0, s[28:29]
	s_nop 0
	v_addc_co_u32_e32 v47, vcc, 0, v113, vcc
	global_store_dwordx4 v[46:47], v[40:43], off sc1
	v_pk_mul_f32 v[4:5], v[4:5], v[156:157] op_sel_hi:[1,0]
	s_nop 0
	v_pk_mul_f32 v[40:41], v[30:31], v[160:161] op_sel_hi:[1,0]
	v_pk_mul_f32 v[30:31], v[28:29], v[160:161] op_sel_hi:[1,0]
	v_cvt_pk_bf16_f32 v28, v36, v37
	v_cvt_pk_bf16_f32 v29, v38, v39
	s_nop 0
	v_cvt_pk_bf16_f32 v30, v30, v31
	v_cvt_pk_bf16_f32 v31, v40, v41
	global_store_dwordx4 v[44:45], v[28:31], off offset:256 sc1
	s_nop 1
	v_pk_mul_f32 v[30:31], v[34:35], v[158:159] op_sel_hi:[1,0]
	v_pk_mul_f32 v[34:35], v[26:27], v[158:159] op_sel_hi:[1,0]
	v_pk_mul_f32 v[26:27], v[24:25], v[158:159] op_sel_hi:[1,0]
	v_cvt_pk_bf16_f32 v24, v32, v33
	v_cvt_pk_bf16_f32 v25, v30, v31
	v_add_co_u32_e32 v30, vcc, s5, v112
	v_cvt_pk_bf16_f32 v26, v26, v27
	v_cvt_pk_bf16_f32 v27, v34, v35
	v_lshl_add_u64 v[28:29], v[112:113], 0, s[30:31]
	s_nop 0
	v_addc_co_u32_e32 v31, vcc, 0, v113, vcc
	global_store_dwordx4 v[30:31], v[24:27], off sc1
	s_nop 1
	v_pk_mul_f32 v[24:25], v[14:15], v[158:159] op_sel_hi:[1,0]
	v_pk_mul_f32 v[14:15], v[12:13], v[158:159] op_sel_hi:[1,0]
	v_cvt_pk_bf16_f32 v12, v20, v21
	v_cvt_pk_bf16_f32 v13, v22, v23
	s_nop 0
	v_cvt_pk_bf16_f32 v14, v14, v15
	v_cvt_pk_bf16_f32 v15, v24, v25
	global_store_dwordx4 v[28:29], v[12:15], off offset:256 sc1
	s_nop 1
	v_pk_mul_f32 v[14:15], v[18:19], v[156:157] op_sel_hi:[1,0]
	v_pk_mul_f32 v[18:19], v[10:11], v[156:157] op_sel_hi:[1,0]
	v_pk_mul_f32 v[10:11], v[8:9], v[156:157] op_sel_hi:[1,0]
	v_cvt_pk_bf16_f32 v8, v16, v17
	v_cvt_pk_bf16_f32 v9, v14, v15
	v_add_co_u32_e32 v14, vcc, s54, v112
	v_lshl_add_u64 v[12:13], v[112:113], 0, s[34:35]
	s_nop 0
	v_addc_co_u32_e32 v15, vcc, 0, v113, vcc
	v_cvt_pk_bf16_f32 v10, v10, v11
	v_cvt_pk_bf16_f32 v11, v18, v19
	global_store_dwordx4 v[14:15], v[8:11], off sc1
	s_nop 1
	v_pk_mul_f32 v[8:9], v[2:3], v[156:157] op_sel_hi:[1,0]
	v_pk_mul_f32 v[2:3], v[0:1], v[156:157] op_sel_hi:[1,0]
	v_cvt_pk_bf16_f32 v0, v4, v5
	v_cvt_pk_bf16_f32 v1, v6, v7
	s_nop 0
	v_cvt_pk_bf16_f32 v2, v2, v3
	v_cvt_pk_bf16_f32 v3, v8, v9
	global_store_dwordx4 v[12:13], v[0:3], off offset:256 sc1
	s_andn2_b64 vcc, exec, s[8:9]
	s_mov_b64 s[8:9], -1
	s_cbranch_vccnz .LBB0_1204

; __device__ __forceinline__ unsigned cvt_pk_bf16(float lo, float hi) { unsigned r; asm volatile("v_cvt_pk_bf16_f32 %0, %1, %2" : "=v"(r) : "v"(lo), "v"(hi)); return r; }
;     __device__ __forceinline__ void operator()(const f32x4 (&acc)[2][2][4][2], const Unit& u, int wr, int wc, int fr, int fq) const {
;     ...
;         const int row0 = u.rb + wr * 64 + fr;
;         float rs[2][4];
; #pragma unroll
;         for (int ai = 0; ai < 2; ++ai) if (ai == 0 || !u.half)
; #pragma unroll
;             for (int m = 0; m < 4; ++m) rs[ai][m] = rsqrtf(SS[row0 + (u.half ? 0 : ai * HALF) + m * 16] * (1.f / 1024.f) + 1e-6f);
;         if (u.pn < 4) {
;             const int col0 = u.cb + wc * 32 + 8 * fq;
; #pragma unroll
;             for (int ai = 0; ai < 2; ++ai) if (ai == 0 || !u.half)
; #pragma unroll
;                 for (int m = 0; m < 4; ++m) { bf16_t* rowp = Q + (size_t)(row0 + ai * HALF + m * 16) * 1024 + col0;
; #pragma unroll
;                     for (int bj = 0; bj < 2; ++bj) if (bj == 0 || !u.q) { const f32x4 v0 = acc[ai][bj][m][0] * rs[ai][m], v1 = acc[ai][bj][m][1] * rs[ai][m];
;                         u32x4 w; w.x = cvt_pk_bf16(v0[0], v0[1]); w.y = cvt_pk_bf16(v0[2], v0[3]); w.z = cvt_pk_bf16(v1[0], v1[1]); w.w = cvt_pk_bf16(v1[2], v1[3]);
;                         *(u32x4*)(rowp + bj * HALF) = w; } }
;         } else {
;             const int col0 = (u.cb - 1024) + wc * 32 + 8 * fq;
; #pragma unroll
;             for (int ai = 0; ai < 2; ++ai) if (ai == 0 || !u.half)
; #pragma unroll
;                 for (int m = 0; m < 4; ++m) { float* rowp = KV + (size_t)(row0 + ai * HALF + m * 16) * 512 + col0;
; #pragma unroll
;                     for (int bj = 0; bj < 2; ++bj) if (bj == 0 || !u.q) { *(f32x4*)(rowp + bj * HALF) = acc[ai][bj][m][0] * rs[ai][m]; *(f32x4*)(rowp + bj * HALF + 4) = acc[ai][bj][m][1] * rs[ai][m]; } }
.LBB0_1232:
	s_and_b64 vcc, exec, s[2:3]
	s_cbranch_vccz .LBB0_1221
	v_mov_b32_e32 v1, v98
	v_mov_b32_e32 v6, v89
	s_add_i32 s21, s21, s4
	s_lshl_b32 s0, s12, 6
	v_add_u32_e32 v14, s21, v6
	v_ashrrev_i32_e32 v15, 31, v14
	v_lshl_add_u64 v[6:7], v[14:15], 2, s[10:11]
	global_load_dword v8, v[6:7], off
	s_cmpk_gt_i32 s20, 0x7f
	v_lshl_add_u32 v1, v1, 3, s0
	s_waitcnt vmcnt(5)
	v_lshlrev_b64 v[32:33], 11, v[14:15]
	s_mov_b64 s[0:1], -1
	s_waitcnt vmcnt(0)
	v_fmamk_f32 v8, v8, 0x3a800000, v109
	v_cmp_gt_f32_e32 vcc, s18, v8
	v_mul_f32_e32 v9, 0x4b800000, v8
	s_nop 0
	v_cndmask_b32_e32 v8, v8, v9, vcc
	v_rsq_f32_e32 v8, v8
	s_nop 0
	v_mul_f32_e32 v9, 0x45800000, v8
	v_cndmask_b32_e32 v16, v8, v9, vcc
	global_load_dword v8, v[6:7], off offset:64
	v_mov_b32_e32 v17, v16
	v_pk_mul_f32 v[10:11], v[62:63], v[16:17]
	s_waitcnt vmcnt(0)
	v_fmamk_f32 v8, v8, 0x3a800000, v109
	v_cmp_gt_f32_e32 vcc, s18, v8
	v_mul_f32_e32 v9, 0x4b800000, v8
	s_nop 0
	v_cndmask_b32_e32 v8, v8, v9, vcc
	v_rsq_f32_e32 v8, v8
	s_nop 0
	v_mul_f32_e32 v9, 0x45800000, v8
	v_cndmask_b32_e32 v18, v8, v9, vcc
	global_load_dword v8, v[6:7], off offset:128
	s_waitcnt vmcnt(0)
	v_fmamk_f32 v8, v8, 0x3a800000, v109
	global_load_dword v6, v[6:7], off offset:192
	v_cmp_gt_f32_e32 vcc, s18, v8
	v_mul_f32_e32 v9, 0x4b800000, v8
	s_waitcnt vmcnt(0)
	v_fmamk_f32 v6, v6, 0x3a800000, v109
	v_cndmask_b32_e32 v8, v8, v9, vcc
	v_rsq_f32_e32 v8, v8
	v_mul_f32_e32 v7, 0x4b800000, v6
	v_mul_f32_e32 v9, 0x45800000, v8
	v_cndmask_b32_e32 v20, v8, v9, vcc
	v_cmp_gt_f32_e32 vcc, s18, v6
	v_pk_mul_f32 v[8:9], v[80:81], v[16:17] op_sel_hi:[1,0]
	s_nop 0
	v_cndmask_b32_e32 v6, v6, v7, vcc
	v_rsq_f32_e32 v6, v6
	s_nop 0
	v_mul_f32_e32 v7, 0x45800000, v6
	v_cndmask_b32_e32 v30, v6, v7, vcc
	v_pk_mul_f32 v[6:7], v[78:79], v[16:17] op_sel_hi:[1,0]
	s_cbranch_scc0 .LBB0_1235
	v_add_u32_e32 v12, s6, v1
	v_readlane_b32 s0, v240, 58
	v_ashrrev_i32_e32 v13, 31, v12
	v_readlane_b32 s1, v240, 59
	v_lshlrev_b64 v[12:13], 2, v[12:13]
	v_mov_b32_e32 v17, v16
	v_lshl_add_u64 v[34:35], s[0:1], 0, v[32:33]
	v_lshl_add_u64 v[38:39], v[34:35], 0, v[12:13]
	v_add_co_u32_e32 v40, vcc, s7, v38
	v_pk_mul_f32 v[12:13], v[64:65], v[16:17]
	s_mov_b64 s[0:1], 0x8000
	v_pk_mul_f32 v[36:37], v[52:53], v[18:19] op_sel_hi:[1,0]
	v_pk_mul_f32 v[34:35], v[50:51], v[18:19] op_sel_hi:[1,0]
	v_addc_co_u32_e32 v41, vcc, 0, v39, vcc
	global_store_dwordx4 v[38:39], v[10:13], off offset:16 sc1
	global_store_dwordx4 v[40:41], v[34:37], off sc1
	v_add_co_u32_e32 v40, vcc, s19, v38
	v_lshl_add_u64 v[12:13], v[38:39], 0, s[0:1]
	v_pk_mul_f32 v[36:37], v[44:45], v[18:19] op_sel_hi:[1,0]
	v_pk_mul_f32 v[34:35], v[42:43], v[18:19] op_sel_hi:[1,0]
	global_store_dwordx4 v[12:13], v[34:37], off offset:16 sc1
	s_mov_b64 s[0:1], 0x10000
	v_addc_co_u32_e32 v41, vcc, 0, v39, vcc
	v_pk_mul_f32 v[36:37], v[28:29], v[20:21] op_sel_hi:[1,0]
	v_pk_mul_f32 v[34:35], v[26:27], v[20:21] op_sel_hi:[1,0]
	v_lshl_add_u64 v[12:13], v[38:39], 0, s[0:1]
	global_store_dwordx4 v[40:41], v[34:37], off sc1
	s_mov_b64 s[0:1], 0x18000
	global_store_dwordx4 v[38:39], v[6:9], off sc1
	v_pk_mul_f32 v[36:37], v[24:25], v[20:21] op_sel_hi:[1,0]
	v_pk_mul_f32 v[34:35], v[22:23], v[20:21] op_sel_hi:[1,0]
	global_store_dwordx4 v[12:13], v[34:37], off offset:16 sc1
	v_lshl_add_u64 v[12:13], v[38:39], 0, s[0:1]
	v_add_co_u32_e32 v38, vcc, 0x18000, v38
	v_pk_mul_f32 v[36:37], v[68:69], v[30:31] op_sel_hi:[1,0]
	v_pk_mul_f32 v[34:35], v[66:67], v[30:31] op_sel_hi:[1,0]
	v_addc_co_u32_e32 v39, vcc, 0, v39, vcc
	global_store_dwordx4 v[38:39], v[34:37], off sc1
	s_mov_b64 s[0:1], 0
	s_nop 0
	v_pk_mul_f32 v[36:37], v[4:5], v[30:31] op_sel_hi:[1,0]
	v_pk_mul_f32 v[34:35], v[2:3], v[30:31] op_sel_hi:[1,0]
	global_store_dwordx4 v[12:13], v[34:37], off offset:16 sc1
.LBB0_1235:
	s_andn2_b64 vcc, exec, s[0:1]
	s_cbranch_vccnz .LBB0_1221
	v_add_u32_e32 v12, s5, v1
	v_readlane_b32 s0, v240, 12
	v_ashrrev_i32_e32 v13, 31, v12
	v_readlane_b32 s1, v240, 13
	v_lshlrev_b64 v[12:13], 1, v[12:13]
	v_mov_b32_e32 v17, v16
	v_lshl_add_u64 v[32:33], s[0:1], 0, v[32:33]
	v_lshl_add_u64 v[32:33], v[32:33], 0, v[12:13]
	v_pk_mul_f32 v[16:17], v[64:65], v[16:17]
	v_cvt_pk_bf16_f32 v6, v6, v7
	v_cvt_pk_bf16_f32 v7, v8, v9
	v_cvt_pk_bf16_f32 v8, v10, v11
	v_pk_mul_f32 v[10:11], v[44:45], v[18:19] op_sel_hi:[1,0]
	v_cvt_pk_bf16_f32 v9, v16, v17
	global_store_dwordx4 v[32:33], v[6:9], off sc1
	v_pk_mul_f32 v[16:17], v[42:43], v[18:19] op_sel_hi:[1,0]
	s_nop 0
	v_pk_mul_f32 v[8:9], v[52:53], v[18:19] op_sel_hi:[1,0]
	v_pk_mul_f32 v[6:7], v[50:51], v[18:19] op_sel_hi:[1,0]
	s_nop 0
	v_cvt_pk_bf16_f32 v6, v6, v7
	v_cvt_pk_bf16_f32 v7, v8, v9
	v_cvt_pk_bf16_f32 v8, v16, v17
	v_cvt_pk_bf16_f32 v9, v10, v11
	v_lshlrev_b64 v[10:11], 11, v[14:15]
	v_lshl_add_u64 v[10:11], s[0:1], 0, v[10:11]
	v_lshl_add_u64 v[10:11], v[10:11], 0, v[12:13]
	v_add_co_u32_e32 v12, vcc, s7, v10
	v_pk_mul_f32 v[14:15], v[22:23], v[20:21] op_sel_hi:[1,0]
	s_nop 0
	v_addc_co_u32_e32 v13, vcc, 0, v11, vcc
	global_store_dwordx4 v[12:13], v[6:9], off sc1
	v_pk_mul_f32 v[12:13], v[24:25], v[20:21] op_sel_hi:[1,0]
	s_nop 0
	v_pk_mul_f32 v[8:9], v[28:29], v[20:21] op_sel_hi:[1,0]
	v_pk_mul_f32 v[6:7], v[26:27], v[20:21] op_sel_hi:[1,0]
	s_nop 0
	v_cvt_pk_bf16_f32 v6, v6, v7
	v_cvt_pk_bf16_f32 v7, v8, v9
	v_cvt_pk_bf16_f32 v8, v14, v15
	v_cvt_pk_bf16_f32 v9, v12, v13
	v_add_co_u32_e32 v12, vcc, s19, v10
	s_nop 1
	v_addc_co_u32_e32 v13, vcc, 0, v11, vcc
	global_store_dwordx4 v[12:13], v[6:9], off sc1
	v_pk_mul_f32 v[12:13], v[4:5], v[30:31] op_sel_hi:[1,0]
	v_pk_mul_f32 v[4:5], v[2:3], v[30:31] op_sel_hi:[1,0]
	v_pk_mul_f32 v[6:7], v[68:69], v[30:31] op_sel_hi:[1,0]
	v_pk_mul_f32 v[8:9], v[66:67], v[30:31] op_sel_hi:[1,0]
	s_nop 0
	v_cvt_pk_bf16_f32 v2, v8, v9
	v_cvt_pk_bf16_f32 v3, v6, v7
	v_add_co_u32_e32 v6, vcc, 0x18000, v10
	v_cvt_pk_bf16_f32 v4, v4, v5
	v_cvt_pk_bf16_f32 v5, v12, v13
	s_nop 1
	v_addc_co_u32_e32 v7, vcc, 0, v11, vcc
	global_store_dwordx4 v[6:7], v[2:5], off sc1
	s_branch .LBB0_1221

; __device__ __forceinline__ unsigned cvt_pk_bf16(float lo, float hi) { unsigned r; asm volatile("v_cvt_pk_bf16_f32 %0, %1, %2" : "=v"(r) : "v"(lo), "v"(hi)); return r; }
;     __device__ __forceinline__ void row_out(const f32x4 v0, const f32x4 v1, int row, int col, float& ss) const {
;         if (C) { float* rowp = C + (size_t)row * ldc + col; __builtin_nontemporal_store(v0, (f32x4*)rowp); __builtin_nontemporal_store(v1, (f32x4*)(rowp + 4)); }
;         if (wxb) { u32x4 w; w.x = cvt_pk_bf16(v0[0], v0[1]); w.y = cvt_pk_bf16(v0[2], v0[3]); w.z = cvt_pk_bf16(v1[0], v1[1]); w.w = cvt_pk_bf16(v1[2], v1[3]);
;             *(u32x4*)(XB0 + (size_t)row * ldc + col) = w;
;             ss += (v0[0] * v0[0] + v0[1] * v0[1]) + (v0[2] * v0[2] + v0[3] * v0[3]) + (v1[0] * v1[0] + v1[1] * v1[1]) + (v1[2] * v1[2] + v1[3] * v1[3]); }
;     }
;     __device__ __forceinline__ void operator()(const f32x4 (&acc)[2][2][4][2], const Unit& u, int wr, int wc, int fr, int fq) const {
;     ...
;               for (int mh = 0; mh < 4; mh += 2) {
;                 u32x4 rw[2][2];
; #pragma unroll
;                 for (int mm = 0; mm < 2; ++mm) { const int row = row0 + ai * HALF + (mh + mm) * 16;
; #pragma unroll
;                     for (int bj = 0; bj < 2; ++bj) if (bj == 0 || !u.q) rw[mm][bj] = *(const u32x4*)(XB0 + (size_t)row * ldc + col0 + bj * HALF); }
; #pragma unroll
;                 for (int mm = 0; mm < 2; ++mm) { const int m = mh + mm, row = row0 + ai * HALF + m * 16; float ss = 0.f;
; #pragma unroll
;                     for (int bj = 0; bj < 2; ++bj) if (bj == 0 || !u.q) { const u32x4 w = rw[mm][bj];
;                         const f32x4 v0 = acc[ai][bj][m][0] + (f32x4){bf_lo(w.x), bf_hi(w.x), bf_lo(w.y), bf_hi(w.y)}, v1 = acc[ai][bj][m][1] + (f32x4){bf_lo(w.z), bf_hi(w.z), bf_lo(w.w), bf_hi(w.w)};
;                         row_out(v0, v1, row, col0 + bj * HALF, ss); }
;                     if (wxb) { ss += __shfl_xor(ss, 16); ss += __shfl_xor(ss, 32); if (fq == 0) unsafeAtomicAdd(SS + row, ss); } }
.LBB0_2496:
	v_mov_b32_e32 v128, v163
	v_mov_b32_e32 v169, v162
	s_add_i32 s0, s0, s33
	v_and_b32_e32 v183, 64, v168
	v_add_u32_e32 v154, s0, v128
	s_add_i32 s0, s40, s34
	v_lshl_add_u32 v152, v169, 3, s0
	v_ashrrev_i32_e32 v153, 31, v152
	v_lshlrev_b64 v[178:179], 1, v[152:153]
	v_ashrrev_i32_e32 v155, 31, v154
	v_lshl_add_u64 v[156:157], s[96:97], 0, v[178:179]
	v_lshlrev_b64 v[180:181], 11, v[154:155]
	v_lshl_add_u64 v[128:129], v[156:157], 0, v[180:181]
	global_load_dwordx4 v[170:173], v[128:129], off
	global_load_dwordx4 v[174:177], v[128:129], off offset:256
	v_add_u32_e32 v158, 16, v154
	v_ashrrev_i32_e32 v159, 31, v158
	v_lshlrev_b64 v[160:161], 11, v[158:159]
	v_lshl_add_u64 v[128:129], v[156:157], 0, v[160:161]
	global_load_dwordx4 v[132:135], v[128:129], off
	s_nop 0
	global_load_dwordx4 v[128:131], v[128:129], off offset:256
	v_xor_b32_e32 v182, 16, v168
	v_add_u32_e32 v183, 64, v183
	v_xor_b32_e32 v184, 32, v168
	v_cmp_lt_i32_e64 s[0:1], v182, v183
	v_cmp_eq_u32_e32 vcc, 0, v169
	v_lshl_add_u64 v[180:181], s[96:97], 0, v[180:181]
	v_cndmask_b32_e64 v169, v168, v182, s[0:1]
	v_cmp_lt_i32_e64 s[0:1], v184, v183
	v_lshl_add_u64 v[178:179], v[180:181], 0, v[178:179]
	v_lshlrev_b32_e32 v169, 2, v169
	v_cndmask_b32_e64 v188, v168, v184, s[0:1]
	s_waitcnt vmcnt(0)
	v_lshlrev_b32_e32 v180, 16, v170
	v_and_b32_e32 v181, 0xffff0000, v170
	v_lshlrev_b32_e32 v170, 16, v171
	v_and_b32_e32 v171, 0xffff0000, v171
	v_lshlrev_b32_e32 v184, 16, v174
	v_and_b32_e32 v185, 0xffff0000, v174
	v_lshlrev_b32_e32 v174, 16, v175
	v_and_b32_e32 v175, 0xffff0000, v175
	v_lshlrev_b32_e32 v182, 16, v172
	v_and_b32_e32 v183, 0xffff0000, v172
	v_lshlrev_b32_e32 v172, 16, v173
	v_and_b32_e32 v173, 0xffff0000, v173
	v_lshlrev_b32_e32 v186, 16, v176
	v_and_b32_e32 v187, 0xffff0000, v176
	v_lshlrev_b32_e32 v176, 16, v177
	v_and_b32_e32 v177, 0xffff0000, v177
	v_pk_add_f32 v[126:127], v[126:127], v[170:171]
	v_pk_add_f32 v[124:125], v[124:125], v[180:181]
	v_pk_add_f32 v[118:119], v[118:119], v[174:175]
	v_pk_add_f32 v[116:117], v[116:117], v[184:185]
	v_pk_add_f32 v[122:123], v[122:123], v[172:173]
	v_pk_add_f32 v[120:121], v[120:121], v[182:183]
	v_pk_add_f32 v[170:171], v[114:115], v[176:177]
	v_pk_add_f32 v[172:173], v[112:113], v[186:187]
	v_mul_f32_e32 v114, v125, v125
	v_mul_f32_e32 v115, v127, v127
	v_mul_f32_e32 v176, v117, v117
	v_mul_f32_e32 v177, v119, v119
	v_cvt_pk_bf16_f32 v112, v124, v125
	v_mul_f32_e32 v125, v121, v121
	v_mul_f32_e32 v175, v173, v173
	v_fmac_f32_e32 v114, v124, v124
	v_fmac_f32_e32 v115, v126, v126
	v_fmac_f32_e32 v176, v116, v116
	v_fmac_f32_e32 v177, v118, v118
	v_cvt_pk_bf16_f32 v113, v126, v127
	v_mul_f32_e32 v127, v123, v123
	v_mul_f32_e32 v174, v171, v171
	v_fmac_f32_e32 v125, v120, v120
	v_fmac_f32_e32 v175, v172, v172
	v_add_f32_e32 v114, v114, v115
	v_add_f32_e32 v115, v176, v177
	v_fmac_f32_e32 v127, v122, v122
	v_fmac_f32_e32 v174, v170, v170
	v_add_f32_e32 v114, v125, v114
	v_add_f32_e32 v115, v175, v115
	v_add_f32_e32 v114, v127, v114
	v_add_f32_e32 v115, v174, v115
	v_add_f32_e32 v124, v114, v115
	ds_bpermute_b32 v125, v169, v124
	v_cvt_pk_bf16_f32 v114, v120, v121
	v_cvt_pk_bf16_f32 v115, v122, v123
	global_store_dwordx4 v[178:179], v[112:115], off sc1
	v_cvt_pk_bf16_f32 v116, v116, v117
	v_cvt_pk_bf16_f32 v117, v118, v119
	v_cvt_pk_bf16_f32 v118, v172, v173
	v_cvt_pk_bf16_f32 v119, v170, v171
	global_store_dwordx4 v[178:179], v[116:119], off offset:256 sc1
	s_waitcnt lgkmcnt(0)
	v_add_f32_e32 v113, v124, v125
	v_lshlrev_b32_e32 v112, 2, v188
	ds_bpermute_b32 v114, v112, v113
	s_and_saveexec_b64 s[0:1], vcc
	s_cbranch_execz .LBB0_2498
	s_waitcnt lgkmcnt(0)
	v_add_f32_e32 v113, v113, v114
	v_lshl_add_u64 v[114:115], v[154:155], 2, s[12:13]
	global_atomic_add_f32 v[114:115], v113, off

; __device__ __forceinline__ unsigned cvt_pk_bf16(float lo, float hi) { unsigned r; asm volatile("v_cvt_pk_bf16_f32 %0, %1, %2" : "=v"(r) : "v"(lo), "v"(hi)); return r; }
; __device__ __forceinline__ f32x2 gelu_pk(f32x2 v) {
;     f32x2 x = v * 0.70710678118f;
;     x.x = __builtin_amdgcn_fmed3f(x.x, -2.9f, 2.9f); x.y = __builtin_amdgcn_fmed3f(x.y, -2.9f, 2.9f);
;     const f32x2 t = x * x;
;     f32x2 p = t * (-4.953124630e-07f) + 1.987094038e-05f;
;     p = p * t + (-3.472001117e-04f); p = p * t + 3.517547622e-03f; p = p * t + (-2.333305031e-02f); p = p * t + 1.087993085e-01f; p = p * t + (-3.740358949e-01f); p = p * t + 1.128076553e+00f;
;     const f32x2 hv = v * 0.5f;
;     return hv * (x * p) + hv;
; }
;     __device__ __forceinline__ void operator()(const f32x4 (&acc)[2][2][4][2], const Unit& u, int wr, int wc, int fr, int fq) const {
;     ...
;             for (int m = 0; m < 4; ++m) { bf16_t* rowp = O + (size_t)(row0 + ai * HALF + m * 16) * ldc + col0;
;                 const float rs = rsqrtf(rsv[ai][m] * (1.f / 1024.f) + 1e-6f);
; #pragma unroll
;                 for (int bj = 0; bj < 2; ++bj) if (bj == 0 || !u.q) { f32x4 v0 = acc[ai][bj][m][0] * rs, v1 = acc[ai][bj][m][1] * rs;
;                     if (act) { f32x2 a = gelu_pk((f32x2){v0[0], v0[1]}), b = gelu_pk((f32x2){v0[2], v0[3]}), c = gelu_pk((f32x2){v1[0], v1[1]}), d = gelu_pk((f32x2){v1[2], v1[3]});
;                         v0 = (f32x4){a.x, a.y, b.x, b.y}; v1 = (f32x4){c.x, c.y, d.x, d.y}; }
;                     u32x4 w; w.x = cvt_pk_bf16(v0[0], v0[1]); w.y = cvt_pk_bf16(v0[2], v0[3]); w.z = cvt_pk_bf16(v1[0], v1[1]); w.w = cvt_pk_bf16(v1[2], v1[3]);
;                     *(u32x4*)(rowp + bj * HALF) = w; } }
.LBB0_2615:
	s_add_i32 s2, s55, s29
	v_lshl_add_u32 v120, v181, 3, s2
	v_lshlrev_b64 v[122:123], 10, v[158:159]
	v_ashrrev_i32_e32 v121, 31, v120
	v_lshl_add_u64 v[122:123], s[64:65], 0, v[122:123]
	v_lshl_add_u64 v[122:123], v[120:121], 1, v[122:123]
	v_cvt_pk_bf16_f32 v124, v124, v125
	v_cvt_pk_bf16_f32 v125, v126, v127
	v_cvt_pk_bf16_f32 v126, v164, v165
	v_cvt_pk_bf16_f32 v127, v162, v163
	global_store_dwordx4 v[122:123], v[124:127], off sc1
	v_mov_b32_e32 v161, v160
	v_pk_mul_f32 v[116:117], v[116:117], v[160:161]
	v_mov_b32_e32 v124, v160
	v_mov_b32_e32 v125, v160
	v_pk_mul_f32 v[118:119], v[118:119], v[124:125]
	v_pk_mul_f32 v[114:115], v[114:115], v[124:125]
	v_cndmask_b32_e64 v124, 0, 1, s[46:47]
	v_cmp_ne_u32_e64 s[10:11], 1, v124
	s_andn2_b64 vcc, exec, s[46:47]
	v_pk_mul_f32 v[112:113], v[112:113], v[160:161]
	s_cbranch_vccnz .LBB0_2617
	v_pk_mul_f32 v[124:125], v[116:117], s[18:19] op_sel_hi:[1,0]
	v_mov_b64_e32 v[158:159], s[22:23]
	v_med3_f32 v124, v124, s53, v173
	v_med3_f32 v125, v125, s53, v173
	v_pk_mul_f32 v[126:127], v[124:125], v[124:125]
	v_pk_mul_f32 v[116:117], v[116:117], 0.5 op_sel_hi:[1,0]
	v_pk_fma_f32 v[160:161], v[126:127], s[20:21], v[158:159] op_sel_hi:[1,0,0] neg_lo:[1,0,0] neg_hi:[1,0,0]
	s_nop 0
	v_pk_fma_f32 v[160:161], v[126:127], v[160:161], s[24:25] op_sel_hi:[1,1,0]
	s_nop 0
	v_pk_fma_f32 v[160:161], v[126:127], v[160:161], s[26:27] op_sel_hi:[1,1,0]
	s_nop 0
	v_pk_fma_f32 v[160:161], v[126:127], v[160:161], s[28:29] op_sel_hi:[1,1,0]
	s_nop 0
	v_pk_fma_f32 v[160:161], v[126:127], v[160:161], s[30:31] op_sel_hi:[1,1,0]
	s_nop 0
	v_pk_fma_f32 v[160:161], v[126:127], v[160:161], s[34:35] op_sel_hi:[1,1,0]
	s_nop 0
	v_pk_fma_f32 v[126:127], v[126:127], v[160:161], s[36:37] op_sel_hi:[1,1,0]
	s_nop 0
	v_pk_mul_f32 v[124:125], v[124:125], v[126:127]
	s_nop 0
	v_pk_fma_f32 v[116:117], v[116:117], v[124:125], v[116:117]
	v_pk_mul_f32 v[124:125], v[118:119], s[18:19] op_sel_hi:[1,0]
	v_pk_mul_f32 v[118:119], v[118:119], 0.5 op_sel_hi:[1,0]
	v_med3_f32 v124, v124, s53, v173
	v_med3_f32 v125, v125, s53, v173
	v_pk_mul_f32 v[126:127], v[124:125], v[124:125]
	s_nop 0
	v_pk_fma_f32 v[160:161], v[126:127], s[20:21], v[158:159] op_sel_hi:[1,0,0] neg_lo:[1,0,0] neg_hi:[1,0,0]
	s_nop 0
	v_pk_fma_f32 v[160:161], v[126:127], v[160:161], s[24:25] op_sel_hi:[1,1,0]
	s_nop 0
	v_pk_fma_f32 v[160:161], v[126:127], v[160:161], s[26:27] op_sel_hi:[1,1,0]
	s_nop 0
	v_pk_fma_f32 v[160:161], v[126:127], v[160:161], s[28:29] op_sel_hi:[1,1,0]
	s_nop 0
	v_pk_fma_f32 v[160:161], v[126:127], v[160:161], s[30:31] op_sel_hi:[1,1,0]
	s_nop 0
	v_pk_fma_f32 v[160:161], v[126:127], v[160:161], s[34:35] op_sel_hi:[1,1,0]
	s_nop 0
	v_pk_fma_f32 v[126:127], v[126:127], v[160:161], s[36:37] op_sel_hi:[1,1,0]
	s_nop 0
	v_pk_mul_f32 v[124:125], v[124:125], v[126:127]
	s_nop 0
	v_pk_fma_f32 v[118:119], v[118:119], v[124:125], v[118:119]
	v_pk_mul_f32 v[124:125], v[112:113], s[18:19] op_sel_hi:[1,0]
	v_pk_mul_f32 v[112:113], v[112:113], 0.5 op_sel_hi:[1,0]
	v_med3_f32 v124, v124, s53, v173
	v_med3_f32 v125, v125, s53, v173
	v_pk_mul_f32 v[126:127], v[124:125], v[124:125]
	s_nop 0
	v_pk_fma_f32 v[160:161], v[126:127], s[20:21], v[158:159] op_sel_hi:[1,0,0] neg_lo:[1,0,0] neg_hi:[1,0,0]
	s_nop 0
	v_pk_fma_f32 v[160:161], v[126:127], v[160:161], s[24:25] op_sel_hi:[1,1,0]
	s_nop 0
	v_pk_fma_f32 v[160:161], v[126:127], v[160:161], s[26:27] op_sel_hi:[1,1,0]
	s_nop 0
	v_pk_fma_f32 v[160:161], v[126:127], v[160:161], s[28:29] op_sel_hi:[1,1,0]
	s_nop 0
	v_pk_fma_f32 v[160:161], v[126:127], v[160:161], s[30:31] op_sel_hi:[1,1,0]
	s_nop 0
	v_pk_fma_f32 v[160:161], v[126:127], v[160:161], s[34:35] op_sel_hi:[1,1,0]
	s_nop 0
	v_pk_fma_f32 v[126:127], v[126:127], v[160:161], s[36:37] op_sel_hi:[1,1,0]
	s_nop 0
	v_pk_mul_f32 v[124:125], v[124:125], v[126:127]
	s_nop 0
	v_pk_fma_f32 v[112:113], v[112:113], v[124:125], v[112:113]
	v_pk_mul_f32 v[124:125], v[114:115], s[18:19] op_sel_hi:[1,0]
	v_pk_mul_f32 v[114:115], v[114:115], 0.5 op_sel_hi:[1,0]
	v_med3_f32 v124, v124, s53, v173
	v_med3_f32 v125, v125, s53, v173
	v_pk_mul_f32 v[126:127], v[124:125], v[124:125]
	s_nop 0
	v_pk_fma_f32 v[158:159], v[126:127], s[20:21], v[158:159] op_sel_hi:[1,0,0] neg_lo:[1,0,0] neg_hi:[1,0,0]
	s_nop 0
	v_pk_fma_f32 v[158:159], v[126:127], v[158:159], s[24:25] op_sel_hi:[1,1,0]
	s_nop 0
	v_pk_fma_f32 v[158:159], v[126:127], v[158:159], s[26:27] op_sel_hi:[1,1,0]
	s_nop 0
	v_pk_fma_f32 v[158:159], v[126:127], v[158:159], s[28:29] op_sel_hi:[1,1,0]
	s_nop 0
	v_pk_fma_f32 v[158:159], v[126:127], v[158:159], s[30:31] op_sel_hi:[1,1,0]
	s_nop 0
	v_pk_fma_f32 v[158:159], v[126:127], v[158:159], s[34:35] op_sel_hi:[1,1,0]
	s_nop 0
	v_pk_fma_f32 v[126:127], v[126:127], v[158:159], s[36:37] op_sel_hi:[1,1,0]
	s_nop 0
	v_pk_mul_f32 v[124:125], v[124:125], v[126:127]
	s_nop 0
	v_pk_fma_f32 v[114:115], v[114:115], v[124:125], v[114:115]
; __device__ __forceinline__ unsigned cvt_pk_bf16(float lo, float hi) { unsigned r; asm volatile("v_cvt_pk_bf16_f32 %0, %1, %2" : "=v"(r) : "v"(lo), "v"(hi)); return r; }
; __device__ __forceinline__ f32x2 gelu_pk(f32x2 v) {
;     f32x2 x = v * 0.70710678118f;
;     x.x = __builtin_amdgcn_fmed3f(x.x, -2.9f, 2.9f); x.y = __builtin_amdgcn_fmed3f(x.y, -2.9f, 2.9f);
;     const f32x2 t = x * x;
;     f32x2 p = t * (-4.953124630e-07f) + 1.987094038e-05f;
;     p = p * t + (-3.472001117e-04f); p = p * t + 3.517547622e-03f; p = p * t + (-2.333305031e-02f); p = p * t + 1.087993085e-01f; p = p * t + (-3.740358949e-01f); p = p * t + 1.128076553e+00f;
;     const f32x2 hv = v * 0.5f;
;     return hv * (x * p) + hv;
; }
;     __device__ __forceinline__ void operator()(const f32x4 (&acc)[2][2][4][2], const Unit& u, int wr, int wc, int fr, int fq) const {
;     ...
;             for (int m = 0; m < 4; ++m) { bf16_t* rowp = O + (size_t)(row0 + ai * HALF + m * 16) * ldc + col0;
;                 const float rs = rsqrtf(rsv[ai][m] * (1.f / 1024.f) + 1e-6f);
; #pragma unroll
;                 for (int bj = 0; bj < 2; ++bj) if (bj == 0 || !u.q) { f32x4 v0 = acc[ai][bj][m][0] * rs, v1 = acc[ai][bj][m][1] * rs;
;                     if (act) { f32x2 a = gelu_pk((f32x2){v0[0], v0[1]}), b = gelu_pk((f32x2){v0[2], v0[3]}), c = gelu_pk((f32x2){v1[0], v1[1]}), d = gelu_pk((f32x2){v1[2], v1[3]});
;                         v0 = (f32x4){a.x, a.y, b.x, b.y}; v1 = (f32x4){c.x, c.y, d.x, d.y}; }
;                     u32x4 w; w.x = cvt_pk_bf16(v0[0], v0[1]); w.y = cvt_pk_bf16(v0[2], v0[3]); w.z = cvt_pk_bf16(v1[0], v1[1]); w.w = cvt_pk_bf16(v1[2], v1[3]);
;                     *(u32x4*)(rowp + bj * HALF) = w; } }
.LBB0_2617:
	v_cvt_pk_bf16_f32 v116, v116, v117
	v_cvt_pk_bf16_f32 v117, v118, v119
	v_fmamk_f32 v118, v180, 0x3a800000, v172
	v_mul_f32_e32 v119, 0x4b800000, v118
	v_cmp_gt_f32_e32 vcc, s52, v118
	v_readlane_b32 s63, v240, 16
	s_nop 0
	v_cndmask_b32_e32 v118, v118, v119, vcc
	v_rsq_f32_e32 v124, v118
	v_cvt_pk_bf16_f32 v118, v112, v113
	v_cvt_pk_bf16_f32 v119, v114, v115
	global_store_dwordx4 v[122:123], v[116:119], off offset:256 sc1
	v_mul_f32_e32 v112, 0x45800000, v124
	v_cndmask_b32_e32 v112, v124, v112, vcc
	v_pk_mul_f32 v[110:111], v[110:111], v[112:113] op_sel_hi:[1,0]
	v_pk_mul_f32 v[108:109], v[108:109], v[112:113] op_sel_hi:[1,0]
	v_pk_mul_f32 v[106:107], v[106:107], v[112:113] op_sel_hi:[1,0]
	s_and_b64 vcc, exec, s[10:11]
	v_pk_mul_f32 v[114:115], v[104:105], v[112:113] op_sel_hi:[1,0]
	s_cbranch_vccnz .LBB0_2619
	v_pk_mul_f32 v[104:105], v[108:109], s[18:19] op_sel_hi:[1,0]
	v_mov_b64_e32 v[118:119], s[22:23]
	v_med3_f32 v104, v104, s53, v173
	v_med3_f32 v105, v105, s53, v173
	v_pk_mul_f32 v[116:117], v[104:105], v[104:105]
	v_pk_mul_f32 v[108:109], v[108:109], 0.5 op_sel_hi:[1,0]
	v_pk_fma_f32 v[122:123], v[116:117], s[20:21], v[118:119] op_sel_hi:[1,0,0] neg_lo:[1,0,0] neg_hi:[1,0,0]
	s_nop 0
	v_pk_fma_f32 v[122:123], v[116:117], v[122:123], s[24:25] op_sel_hi:[1,1,0]
	s_nop 0
	v_pk_fma_f32 v[122:123], v[116:117], v[122:123], s[26:27] op_sel_hi:[1,1,0]
	s_nop 0
	v_pk_fma_f32 v[122:123], v[116:117], v[122:123], s[28:29] op_sel_hi:[1,1,0]
	s_nop 0
	v_pk_fma_f32 v[122:123], v[116:117], v[122:123], s[30:31] op_sel_hi:[1,1,0]
	s_nop 0
	v_pk_fma_f32 v[122:123], v[116:117], v[122:123], s[34:35] op_sel_hi:[1,1,0]
	s_nop 0
	v_pk_fma_f32 v[116:117], v[116:117], v[122:123], s[36:37] op_sel_hi:[1,1,0]
	s_nop 0
	v_pk_mul_f32 v[104:105], v[104:105], v[116:117]
	s_nop 0
	v_pk_fma_f32 v[108:109], v[108:109], v[104:105], v[108:109]
	v_pk_mul_f32 v[104:105], v[110:111], s[18:19] op_sel_hi:[1,0]
	v_pk_mul_f32 v[110:111], v[110:111], 0.5 op_sel_hi:[1,0]
	v_med3_f32 v104, v104, s53, v173
	v_med3_f32 v105, v105, s53, v173
	v_pk_mul_f32 v[116:117], v[104:105], v[104:105]
	s_nop 0
	v_pk_fma_f32 v[122:123], v[116:117], s[20:21], v[118:119] op_sel_hi:[1,0,0] neg_lo:[1,0,0] neg_hi:[1,0,0]
	s_nop 0
	v_pk_fma_f32 v[122:123], v[116:117], v[122:123], s[24:25] op_sel_hi:[1,1,0]
	s_nop 0
	v_pk_fma_f32 v[122:123], v[116:117], v[122:123], s[26:27] op_sel_hi:[1,1,0]
	s_nop 0
	v_pk_fma_f32 v[122:123], v[116:117], v[122:123], s[28:29] op_sel_hi:[1,1,0]
	s_nop 0
	v_pk_fma_f32 v[122:123], v[116:117], v[122:123], s[30:31] op_sel_hi:[1,1,0]
	s_nop 0
	v_pk_fma_f32 v[122:123], v[116:117], v[122:123], s[34:35] op_sel_hi:[1,1,0]
	s_nop 0
	v_pk_fma_f32 v[116:117], v[116:117], v[122:123], s[36:37] op_sel_hi:[1,1,0]
	s_nop 0
	v_pk_mul_f32 v[104:105], v[104:105], v[116:117]
	s_nop 0
	v_pk_fma_f32 v[110:111], v[110:111], v[104:105], v[110:111]
	v_pk_mul_f32 v[104:105], v[114:115], s[18:19] op_sel_hi:[1,0]
	v_pk_mul_f32 v[114:115], v[114:115], 0.5 op_sel_hi:[1,0]
	v_med3_f32 v104, v104, s53, v173
	v_med3_f32 v105, v105, s53, v173
	v_pk_mul_f32 v[116:117], v[104:105], v[104:105]
	s_nop 0
	v_pk_fma_f32 v[122:123], v[116:117], s[20:21], v[118:119] op_sel_hi:[1,0,0] neg_lo:[1,0,0] neg_hi:[1,0,0]
	s_nop 0
	v_pk_fma_f32 v[122:123], v[116:117], v[122:123], s[24:25] op_sel_hi:[1,1,0]
	s_nop 0
	v_pk_fma_f32 v[122:123], v[116:117], v[122:123], s[26:27] op_sel_hi:[1,1,0]
	s_nop 0
	v_pk_fma_f32 v[122:123], v[116:117], v[122:123], s[28:29] op_sel_hi:[1,1,0]
	s_nop 0
	v_pk_fma_f32 v[122:123], v[116:117], v[122:123], s[30:31] op_sel_hi:[1,1,0]
	s_nop 0
	v_pk_fma_f32 v[122:123], v[116:117], v[122:123], s[34:35] op_sel_hi:[1,1,0]
	s_nop 0
	v_pk_fma_f32 v[116:117], v[116:117], v[122:123], s[36:37] op_sel_hi:[1,1,0]
	s_nop 0
	v_pk_mul_f32 v[104:105], v[104:105], v[116:117]
	s_nop 0
	v_pk_fma_f32 v[114:115], v[114:115], v[104:105], v[114:115]
	v_pk_mul_f32 v[104:105], v[106:107], s[18:19] op_sel_hi:[1,0]
	v_pk_mul_f32 v[106:107], v[106:107], 0.5 op_sel_hi:[1,0]
	v_med3_f32 v104, v104, s53, v173
	v_med3_f32 v105, v105, s53, v173
	v_pk_mul_f32 v[116:117], v[104:105], v[104:105]
	s_nop 0
	v_pk_fma_f32 v[118:119], v[116:117], s[20:21], v[118:119] op_sel_hi:[1,0,0] neg_lo:[1,0,0] neg_hi:[1,0,0]
	s_nop 0
	v_pk_fma_f32 v[118:119], v[116:117], v[118:119], s[24:25] op_sel_hi:[1,1,0]
	s_nop 0
	v_pk_fma_f32 v[118:119], v[116:117], v[118:119], s[26:27] op_sel_hi:[1,1,0]
	s_nop 0
	v_pk_fma_f32 v[118:119], v[116:117], v[118:119], s[28:29] op_sel_hi:[1,1,0]
	s_nop 0
	v_pk_fma_f32 v[118:119], v[116:117], v[118:119], s[30:31] op_sel_hi:[1,1,0]
	s_nop 0
	v_pk_fma_f32 v[118:119], v[116:117], v[118:119], s[34:35] op_sel_hi:[1,1,0]
	s_nop 0
	v_pk_fma_f32 v[116:117], v[116:117], v[118:119], s[36:37] op_sel_hi:[1,1,0]
	s_nop 0
	v_pk_mul_f32 v[104:105], v[104:105], v[116:117]
	s_nop 0
	v_pk_fma_f32 v[106:107], v[106:107], v[104:105], v[106:107]
; __device__ __forceinline__ unsigned cvt_pk_bf16(float lo, float hi) { unsigned r; asm volatile("v_cvt_pk_bf16_f32 %0, %1, %2" : "=v"(r) : "v"(lo), "v"(hi)); return r; }
; __device__ __forceinline__ f32x2 gelu_pk(f32x2 v) {
;     f32x2 x = v * 0.70710678118f;
;     x.x = __builtin_amdgcn_fmed3f(x.x, -2.9f, 2.9f); x.y = __builtin_amdgcn_fmed3f(x.y, -2.9f, 2.9f);
;     const f32x2 t = x * x;
;     f32x2 p = t * (-4.953124630e-07f) + 1.987094038e-05f;
;     p = p * t + (-3.472001117e-04f); p = p * t + 3.517547622e-03f; p = p * t + (-2.333305031e-02f); p = p * t + 1.087993085e-01f; p = p * t + (-3.740358949e-01f); p = p * t + 1.128076553e+00f;
;     const f32x2 hv = v * 0.5f;
;     return hv * (x * p) + hv;
; }
;     __device__ __forceinline__ void operator()(const f32x4 (&acc)[2][2][4][2], const Unit& u, int wr, int wc, int fr, int fq) const {
;     ...
;             for (int m = 0; m < 4; ++m) { bf16_t* rowp = O + (size_t)(row0 + ai * HALF + m * 16) * ldc + col0;
;                 const float rs = rsqrtf(rsv[ai][m] * (1.f / 1024.f) + 1e-6f);
; #pragma unroll
;                 for (int bj = 0; bj < 2; ++bj) if (bj == 0 || !u.q) { f32x4 v0 = acc[ai][bj][m][0] * rs, v1 = acc[ai][bj][m][1] * rs;
;                     if (act) { f32x2 a = gelu_pk((f32x2){v0[0], v0[1]}), b = gelu_pk((f32x2){v0[2], v0[3]}), c = gelu_pk((f32x2){v1[0], v1[1]}), d = gelu_pk((f32x2){v1[2], v1[3]});
;                         v0 = (f32x4){a.x, a.y, b.x, b.y}; v1 = (f32x4){c.x, c.y, d.x, d.y}; }
;                     u32x4 w; w.x = cvt_pk_bf16(v0[0], v0[1]); w.y = cvt_pk_bf16(v0[2], v0[3]); w.z = cvt_pk_bf16(v1[0], v1[1]); w.w = cvt_pk_bf16(v1[2], v1[3]);
;                     *(u32x4*)(rowp + bj * HALF) = w; } }
.LBB0_2619:
	v_lshlrev_b64 v[104:105], 10, v[156:157]
	v_mov_b32_e32 v113, v112
	v_lshl_add_u64 v[104:105], s[64:65], 0, v[104:105]
	v_cvt_pk_bf16_f32 v108, v108, v109
	v_cvt_pk_bf16_f32 v109, v110, v111
	v_cvt_pk_bf16_f32 v110, v114, v115
	v_cvt_pk_bf16_f32 v111, v106, v107
	v_mov_b32_e32 v106, v112
	v_mov_b32_e32 v107, v112
	v_lshl_add_u64 v[104:105], v[120:121], 1, v[104:105]
	v_pk_mul_f32 v[102:103], v[102:103], v[106:107]
	v_pk_mul_f32 v[100:101], v[100:101], v[112:113]
	v_pk_mul_f32 v[98:99], v[98:99], v[106:107]
	s_and_b64 vcc, exec, s[10:11]
	v_pk_mul_f32 v[96:97], v[96:97], v[112:113]
	global_store_dwordx4 v[104:105], v[108:111], off sc1
	s_cbranch_vccnz .LBB0_2621
	v_pk_mul_f32 v[106:107], v[100:101], s[18:19] op_sel_hi:[1,0]
	v_mov_b64_e32 v[110:111], s[22:23]
	v_med3_f32 v106, v106, s53, v173
	v_med3_f32 v107, v107, s53, v173
	v_pk_mul_f32 v[108:109], v[106:107], v[106:107]
	v_pk_mul_f32 v[100:101], v[100:101], 0.5 op_sel_hi:[1,0]
	v_pk_fma_f32 v[112:113], v[108:109], s[20:21], v[110:111] op_sel_hi:[1,0,0] neg_lo:[1,0,0] neg_hi:[1,0,0]
	s_nop 0
	v_pk_fma_f32 v[112:113], v[108:109], v[112:113], s[24:25] op_sel_hi:[1,1,0]
	s_nop 0
	v_pk_fma_f32 v[112:113], v[108:109], v[112:113], s[26:27] op_sel_hi:[1,1,0]
	s_nop 0
	v_pk_fma_f32 v[112:113], v[108:109], v[112:113], s[28:29] op_sel_hi:[1,1,0]
	s_nop 0
	v_pk_fma_f32 v[112:113], v[108:109], v[112:113], s[30:31] op_sel_hi:[1,1,0]
	s_nop 0
	v_pk_fma_f32 v[112:113], v[108:109], v[112:113], s[34:35] op_sel_hi:[1,1,0]
	s_nop 0
	v_pk_fma_f32 v[108:109], v[108:109], v[112:113], s[36:37] op_sel_hi:[1,1,0]
	s_nop 0
	v_pk_mul_f32 v[106:107], v[106:107], v[108:109]
	s_nop 0
	v_pk_fma_f32 v[100:101], v[100:101], v[106:107], v[100:101]
	v_pk_mul_f32 v[106:107], v[102:103], s[18:19] op_sel_hi:[1,0]
	v_pk_mul_f32 v[102:103], v[102:103], 0.5 op_sel_hi:[1,0]
	v_med3_f32 v106, v106, s53, v173
	v_med3_f32 v107, v107, s53, v173
	v_pk_mul_f32 v[108:109], v[106:107], v[106:107]
	s_nop 0
	v_pk_fma_f32 v[112:113], v[108:109], s[20:21], v[110:111] op_sel_hi:[1,0,0] neg_lo:[1,0,0] neg_hi:[1,0,0]
	s_nop 0
	v_pk_fma_f32 v[112:113], v[108:109], v[112:113], s[24:25] op_sel_hi:[1,1,0]
	s_nop 0
	v_pk_fma_f32 v[112:113], v[108:109], v[112:113], s[26:27] op_sel_hi:[1,1,0]
	s_nop 0
	v_pk_fma_f32 v[112:113], v[108:109], v[112:113], s[28:29] op_sel_hi:[1,1,0]
	s_nop 0
	v_pk_fma_f32 v[112:113], v[108:109], v[112:113], s[30:31] op_sel_hi:[1,1,0]
	s_nop 0
	v_pk_fma_f32 v[112:113], v[108:109], v[112:113], s[34:35] op_sel_hi:[1,1,0]
	s_nop 0
	v_pk_fma_f32 v[108:109], v[108:109], v[112:113], s[36:37] op_sel_hi:[1,1,0]
	s_nop 0
	v_pk_mul_f32 v[106:107], v[106:107], v[108:109]
	s_nop 0
	v_pk_fma_f32 v[102:103], v[102:103], v[106:107], v[102:103]
	v_pk_mul_f32 v[106:107], v[96:97], s[18:19] op_sel_hi:[1,0]
	v_pk_mul_f32 v[96:97], v[96:97], 0.5 op_sel_hi:[1,0]
	v_med3_f32 v106, v106, s53, v173
	v_med3_f32 v107, v107, s53, v173
	v_pk_mul_f32 v[108:109], v[106:107], v[106:107]
	s_nop 0
	v_pk_fma_f32 v[112:113], v[108:109], s[20:21], v[110:111] op_sel_hi:[1,0,0] neg_lo:[1,0,0] neg_hi:[1,0,0]
	s_nop 0
	v_pk_fma_f32 v[112:113], v[108:109], v[112:113], s[24:25] op_sel_hi:[1,1,0]
	s_nop 0
	v_pk_fma_f32 v[112:113], v[108:109], v[112:113], s[26:27] op_sel_hi:[1,1,0]
	s_nop 0
	v_pk_fma_f32 v[112:113], v[108:109], v[112:113], s[28:29] op_sel_hi:[1,1,0]
	s_nop 0
	v_pk_fma_f32 v[112:113], v[108:109], v[112:113], s[30:31] op_sel_hi:[1,1,0]
	s_nop 0
	v_pk_fma_f32 v[112:113], v[108:109], v[112:113], s[34:35] op_sel_hi:[1,1,0]
	s_nop 0
	v_pk_fma_f32 v[108:109], v[108:109], v[112:113], s[36:37] op_sel_hi:[1,1,0]
	s_nop 0
	v_pk_mul_f32 v[106:107], v[106:107], v[108:109]
	s_nop 0
	v_pk_fma_f32 v[96:97], v[96:97], v[106:107], v[96:97]
	v_pk_mul_f32 v[106:107], v[98:99], s[18:19] op_sel_hi:[1,0]
	v_pk_mul_f32 v[98:99], v[98:99], 0.5 op_sel_hi:[1,0]
	v_med3_f32 v106, v106, s53, v173
	v_med3_f32 v107, v107, s53, v173
	v_pk_mul_f32 v[108:109], v[106:107], v[106:107]
	s_nop 0
	v_pk_fma_f32 v[110:111], v[108:109], s[20:21], v[110:111] op_sel_hi:[1,0,0] neg_lo:[1,0,0] neg_hi:[1,0,0]
	s_nop 0
	v_pk_fma_f32 v[110:111], v[108:109], v[110:111], s[24:25] op_sel_hi:[1,1,0]
	s_nop 0
	v_pk_fma_f32 v[110:111], v[108:109], v[110:111], s[26:27] op_sel_hi:[1,1,0]
	s_nop 0
	v_pk_fma_f32 v[110:111], v[108:109], v[110:111], s[28:29] op_sel_hi:[1,1,0]
	s_nop 0
	v_pk_fma_f32 v[110:111], v[108:109], v[110:111], s[30:31] op_sel_hi:[1,1,0]
	s_nop 0
	v_pk_fma_f32 v[110:111], v[108:109], v[110:111], s[34:35] op_sel_hi:[1,1,0]
	s_nop 0
	v_pk_fma_f32 v[108:109], v[108:109], v[110:111], s[36:37] op_sel_hi:[1,1,0]
	s_nop 0
	v_pk_mul_f32 v[106:107], v[106:107], v[108:109]
	s_nop 0
	v_pk_fma_f32 v[98:99], v[98:99], v[106:107], v[98:99]
; __device__ __forceinline__ unsigned cvt_pk_bf16(float lo, float hi) { unsigned r; asm volatile("v_cvt_pk_bf16_f32 %0, %1, %2" : "=v"(r) : "v"(lo), "v"(hi)); return r; }
; __device__ __forceinline__ f32x2 gelu_pk(f32x2 v) {
;     f32x2 x = v * 0.70710678118f;
;     x.x = __builtin_amdgcn_fmed3f(x.x, -2.9f, 2.9f); x.y = __builtin_amdgcn_fmed3f(x.y, -2.9f, 2.9f);
;     const f32x2 t = x * x;
;     f32x2 p = t * (-4.953124630e-07f) + 1.987094038e-05f;
;     p = p * t + (-3.472001117e-04f); p = p * t + 3.517547622e-03f; p = p * t + (-2.333305031e-02f); p = p * t + 1.087993085e-01f; p = p * t + (-3.740358949e-01f); p = p * t + 1.128076553e+00f;
;     const f32x2 hv = v * 0.5f;
;     return hv * (x * p) + hv;
; }
;     __device__ __forceinline__ void operator()(const f32x4 (&acc)[2][2][4][2], const Unit& u, int wr, int wc, int fr, int fq) const {
;     ...
;             for (int m = 0; m < 4; ++m) { bf16_t* rowp = O + (size_t)(row0 + ai * HALF + m * 16) * ldc + col0;
;                 const float rs = rsqrtf(rsv[ai][m] * (1.f / 1024.f) + 1e-6f);
; #pragma unroll
;                 for (int bj = 0; bj < 2; ++bj) if (bj == 0 || !u.q) { f32x4 v0 = acc[ai][bj][m][0] * rs, v1 = acc[ai][bj][m][1] * rs;
;                     if (act) { f32x2 a = gelu_pk((f32x2){v0[0], v0[1]}), b = gelu_pk((f32x2){v0[2], v0[3]}), c = gelu_pk((f32x2){v1[0], v1[1]}), d = gelu_pk((f32x2){v1[2], v1[3]});
;                         v0 = (f32x4){a.x, a.y, b.x, b.y}; v1 = (f32x4){c.x, c.y, d.x, d.y}; }
;                     u32x4 w; w.x = cvt_pk_bf16(v0[0], v0[1]); w.y = cvt_pk_bf16(v0[2], v0[3]); w.z = cvt_pk_bf16(v1[0], v1[1]); w.w = cvt_pk_bf16(v1[2], v1[3]);
;                     *(u32x4*)(rowp + bj * HALF) = w; } }
.LBB0_2621:
	v_cvt_pk_bf16_f32 v100, v100, v101
	v_cvt_pk_bf16_f32 v101, v102, v103
	v_fmamk_f32 v102, v179, 0x3a800000, v172
	v_mul_f32_e32 v103, 0x4b800000, v102
	v_cmp_gt_f32_e32 vcc, s52, v102
	s_nop 1
	v_cndmask_b32_e32 v102, v102, v103, vcc
	v_rsq_f32_e32 v106, v102
	v_cvt_pk_bf16_f32 v102, v96, v97
	v_cvt_pk_bf16_f32 v103, v98, v99
	global_store_dwordx4 v[104:105], v[100:103], off offset:256 sc1
	v_mul_f32_e32 v96, 0x45800000, v106
	v_cndmask_b32_e32 v96, v106, v96, vcc
	v_pk_mul_f32 v[94:95], v[94:95], v[96:97] op_sel_hi:[1,0]
	v_pk_mul_f32 v[92:93], v[92:93], v[96:97] op_sel_hi:[1,0]
	v_pk_mul_f32 v[90:91], v[90:91], v[96:97] op_sel_hi:[1,0]
	s_and_b64 vcc, exec, s[10:11]
	v_pk_mul_f32 v[98:99], v[88:89], v[96:97] op_sel_hi:[1,0]
	s_cbranch_vccnz .LBB0_2623
	v_pk_mul_f32 v[88:89], v[92:93], s[18:19] op_sel_hi:[1,0]
	v_mov_b64_e32 v[102:103], s[22:23]
	v_med3_f32 v88, v88, s53, v173
	v_med3_f32 v89, v89, s53, v173
	v_pk_mul_f32 v[100:101], v[88:89], v[88:89]
	v_pk_mul_f32 v[92:93], v[92:93], 0.5 op_sel_hi:[1,0]
	v_pk_fma_f32 v[104:105], v[100:101], s[20:21], v[102:103] op_sel_hi:[1,0,0] neg_lo:[1,0,0] neg_hi:[1,0,0]
	s_nop 0
	v_pk_fma_f32 v[104:105], v[100:101], v[104:105], s[24:25] op_sel_hi:[1,1,0]
	s_nop 0
	v_pk_fma_f32 v[104:105], v[100:101], v[104:105], s[26:27] op_sel_hi:[1,1,0]
	s_nop 0
	v_pk_fma_f32 v[104:105], v[100:101], v[104:105], s[28:29] op_sel_hi:[1,1,0]
	s_nop 0
	v_pk_fma_f32 v[104:105], v[100:101], v[104:105], s[30:31] op_sel_hi:[1,1,0]
	s_nop 0
	v_pk_fma_f32 v[104:105], v[100:101], v[104:105], s[34:35] op_sel_hi:[1,1,0]
	s_nop 0
	v_pk_fma_f32 v[100:101], v[100:101], v[104:105], s[36:37] op_sel_hi:[1,1,0]
	s_nop 0
	v_pk_mul_f32 v[88:89], v[88:89], v[100:101]
	s_nop 0
	v_pk_fma_f32 v[92:93], v[92:93], v[88:89], v[92:93]
	v_pk_mul_f32 v[88:89], v[94:95], s[18:19] op_sel_hi:[1,0]
	v_pk_mul_f32 v[94:95], v[94:95], 0.5 op_sel_hi:[1,0]
	v_med3_f32 v88, v88, s53, v173
	v_med3_f32 v89, v89, s53, v173
	v_pk_mul_f32 v[100:101], v[88:89], v[88:89]
	s_nop 0
	v_pk_fma_f32 v[104:105], v[100:101], s[20:21], v[102:103] op_sel_hi:[1,0,0] neg_lo:[1,0,0] neg_hi:[1,0,0]
	s_nop 0
	v_pk_fma_f32 v[104:105], v[100:101], v[104:105], s[24:25] op_sel_hi:[1,1,0]
	s_nop 0
	v_pk_fma_f32 v[104:105], v[100:101], v[104:105], s[26:27] op_sel_hi:[1,1,0]
	s_nop 0
	v_pk_fma_f32 v[104:105], v[100:101], v[104:105], s[28:29] op_sel_hi:[1,1,0]
	s_nop 0
	v_pk_fma_f32 v[104:105], v[100:101], v[104:105], s[30:31] op_sel_hi:[1,1,0]
	s_nop 0
	v_pk_fma_f32 v[104:105], v[100:101], v[104:105], s[34:35] op_sel_hi:[1,1,0]
	s_nop 0
	v_pk_fma_f32 v[100:101], v[100:101], v[104:105], s[36:37] op_sel_hi:[1,1,0]
	s_nop 0
	v_pk_mul_f32 v[88:89], v[88:89], v[100:101]
	s_nop 0
	v_pk_fma_f32 v[94:95], v[94:95], v[88:89], v[94:95]
	v_pk_mul_f32 v[88:89], v[98:99], s[18:19] op_sel_hi:[1,0]
	v_pk_mul_f32 v[98:99], v[98:99], 0.5 op_sel_hi:[1,0]
	v_med3_f32 v88, v88, s53, v173
	v_med3_f32 v89, v89, s53, v173
	v_pk_mul_f32 v[100:101], v[88:89], v[88:89]
	s_nop 0
	v_pk_fma_f32 v[104:105], v[100:101], s[20:21], v[102:103] op_sel_hi:[1,0,0] neg_lo:[1,0,0] neg_hi:[1,0,0]
	s_nop 0
	v_pk_fma_f32 v[104:105], v[100:101], v[104:105], s[24:25] op_sel_hi:[1,1,0]
	s_nop 0
	v_pk_fma_f32 v[104:105], v[100:101], v[104:105], s[26:27] op_sel_hi:[1,1,0]
	s_nop 0
	v_pk_fma_f32 v[104:105], v[100:101], v[104:105], s[28:29] op_sel_hi:[1,1,0]
	s_nop 0
	v_pk_fma_f32 v[104:105], v[100:101], v[104:105], s[30:31] op_sel_hi:[1,1,0]
	s_nop 0
	v_pk_fma_f32 v[104:105], v[100:101], v[104:105], s[34:35] op_sel_hi:[1,1,0]
	s_nop 0
	v_pk_fma_f32 v[100:101], v[100:101], v[104:105], s[36:37] op_sel_hi:[1,1,0]
	s_nop 0
	v_pk_mul_f32 v[88:89], v[88:89], v[100:101]
	s_nop 0
	v_pk_fma_f32 v[98:99], v[98:99], v[88:89], v[98:99]
	v_pk_mul_f32 v[88:89], v[90:91], s[18:19] op_sel_hi:[1,0]
	v_pk_mul_f32 v[90:91], v[90:91], 0.5 op_sel_hi:[1,0]
	v_med3_f32 v88, v88, s53, v173
	v_med3_f32 v89, v89, s53, v173
	v_pk_mul_f32 v[100:101], v[88:89], v[88:89]
	s_nop 0
	v_pk_fma_f32 v[102:103], v[100:101], s[20:21], v[102:103] op_sel_hi:[1,0,0] neg_lo:[1,0,0] neg_hi:[1,0,0]
	s_nop 0
	v_pk_fma_f32 v[102:103], v[100:101], v[102:103], s[24:25] op_sel_hi:[1,1,0]
	s_nop 0
	v_pk_fma_f32 v[102:103], v[100:101], v[102:103], s[26:27] op_sel_hi:[1,1,0]
	s_nop 0
	v_pk_fma_f32 v[102:103], v[100:101], v[102:103], s[28:29] op_sel_hi:[1,1,0]
	s_nop 0
	v_pk_fma_f32 v[102:103], v[100:101], v[102:103], s[30:31] op_sel_hi:[1,1,0]
	s_nop 0
	v_pk_fma_f32 v[102:103], v[100:101], v[102:103], s[34:35] op_sel_hi:[1,1,0]
	s_nop 0
	v_pk_fma_f32 v[100:101], v[100:101], v[102:103], s[36:37] op_sel_hi:[1,1,0]
	s_nop 0
	v_pk_mul_f32 v[88:89], v[88:89], v[100:101]
	s_nop 0
	v_pk_fma_f32 v[90:91], v[90:91], v[88:89], v[90:91]
; __device__ __forceinline__ unsigned cvt_pk_bf16(float lo, float hi) { unsigned r; asm volatile("v_cvt_pk_bf16_f32 %0, %1, %2" : "=v"(r) : "v"(lo), "v"(hi)); return r; }
; __device__ __forceinline__ f32x2 gelu_pk(f32x2 v) {
;     f32x2 x = v * 0.70710678118f;
;     x.x = __builtin_amdgcn_fmed3f(x.x, -2.9f, 2.9f); x.y = __builtin_amdgcn_fmed3f(x.y, -2.9f, 2.9f);
;     const f32x2 t = x * x;
;     f32x2 p = t * (-4.953124630e-07f) + 1.987094038e-05f;
;     p = p * t + (-3.472001117e-04f); p = p * t + 3.517547622e-03f; p = p * t + (-2.333305031e-02f); p = p * t + 1.087993085e-01f; p = p * t + (-3.740358949e-01f); p = p * t + 1.128076553e+00f;
;     const f32x2 hv = v * 0.5f;
;     return hv * (x * p) + hv;
; }
;     __device__ __forceinline__ void operator()(const f32x4 (&acc)[2][2][4][2], const Unit& u, int wr, int wc, int fr, int fq) const {
;     ...
;             for (int m = 0; m < 4; ++m) { bf16_t* rowp = O + (size_t)(row0 + ai * HALF + m * 16) * ldc + col0;
;                 const float rs = rsqrtf(rsv[ai][m] * (1.f / 1024.f) + 1e-6f);
; #pragma unroll
;                 for (int bj = 0; bj < 2; ++bj) if (bj == 0 || !u.q) { f32x4 v0 = acc[ai][bj][m][0] * rs, v1 = acc[ai][bj][m][1] * rs;
;                     if (act) { f32x2 a = gelu_pk((f32x2){v0[0], v0[1]}), b = gelu_pk((f32x2){v0[2], v0[3]}), c = gelu_pk((f32x2){v1[0], v1[1]}), d = gelu_pk((f32x2){v1[2], v1[3]});
;                         v0 = (f32x4){a.x, a.y, b.x, b.y}; v1 = (f32x4){c.x, c.y, d.x, d.y}; }
;                     u32x4 w; w.x = cvt_pk_bf16(v0[0], v0[1]); w.y = cvt_pk_bf16(v0[2], v0[3]); w.z = cvt_pk_bf16(v1[0], v1[1]); w.w = cvt_pk_bf16(v1[2], v1[3]);
;                     *(u32x4*)(rowp + bj * HALF) = w; } }
.LBB0_2623:
	v_lshlrev_b64 v[88:89], 10, v[154:155]
	v_mov_b32_e32 v97, v96
	v_lshl_add_u64 v[88:89], s[64:65], 0, v[88:89]
	v_cvt_pk_bf16_f32 v92, v92, v93
	v_cvt_pk_bf16_f32 v93, v94, v95
	v_cvt_pk_bf16_f32 v94, v98, v99
	v_cvt_pk_bf16_f32 v95, v90, v91
	v_mov_b32_e32 v90, v96
	v_mov_b32_e32 v91, v96
	v_lshl_add_u64 v[88:89], v[120:121], 1, v[88:89]
	v_pk_mul_f32 v[86:87], v[86:87], v[90:91]
	v_pk_mul_f32 v[84:85], v[84:85], v[96:97]
	v_pk_mul_f32 v[82:83], v[82:83], v[90:91]
	s_and_b64 vcc, exec, s[10:11]
	v_pk_mul_f32 v[80:81], v[80:81], v[96:97]
	global_store_dwordx4 v[88:89], v[92:95], off sc1
	s_cbranch_vccnz .LBB0_2625
	v_pk_mul_f32 v[90:91], v[84:85], s[18:19] op_sel_hi:[1,0]
	v_mov_b64_e32 v[94:95], s[22:23]
	v_med3_f32 v90, v90, s53, v173
	v_med3_f32 v91, v91, s53, v173
	v_pk_mul_f32 v[92:93], v[90:91], v[90:91]
	v_pk_mul_f32 v[84:85], v[84:85], 0.5 op_sel_hi:[1,0]
	v_pk_fma_f32 v[96:97], v[92:93], s[20:21], v[94:95] op_sel_hi:[1,0,0] neg_lo:[1,0,0] neg_hi:[1,0,0]
	s_nop 0
	v_pk_fma_f32 v[96:97], v[92:93], v[96:97], s[24:25] op_sel_hi:[1,1,0]
	s_nop 0
	v_pk_fma_f32 v[96:97], v[92:93], v[96:97], s[26:27] op_sel_hi:[1,1,0]
	s_nop 0
	v_pk_fma_f32 v[96:97], v[92:93], v[96:97], s[28:29] op_sel_hi:[1,1,0]
	s_nop 0
	v_pk_fma_f32 v[96:97], v[92:93], v[96:97], s[30:31] op_sel_hi:[1,1,0]
	s_nop 0
	v_pk_fma_f32 v[96:97], v[92:93], v[96:97], s[34:35] op_sel_hi:[1,1,0]
	s_nop 0
	v_pk_fma_f32 v[92:93], v[92:93], v[96:97], s[36:37] op_sel_hi:[1,1,0]
	s_nop 0
	v_pk_mul_f32 v[90:91], v[90:91], v[92:93]
	s_nop 0
	v_pk_fma_f32 v[84:85], v[84:85], v[90:91], v[84:85]
	v_pk_mul_f32 v[90:91], v[86:87], s[18:19] op_sel_hi:[1,0]
	v_pk_mul_f32 v[86:87], v[86:87], 0.5 op_sel_hi:[1,0]
	v_med3_f32 v90, v90, s53, v173
	v_med3_f32 v91, v91, s53, v173
	v_pk_mul_f32 v[92:93], v[90:91], v[90:91]
	s_nop 0
	v_pk_fma_f32 v[96:97], v[92:93], s[20:21], v[94:95] op_sel_hi:[1,0,0] neg_lo:[1,0,0] neg_hi:[1,0,0]
	s_nop 0
	v_pk_fma_f32 v[96:97], v[92:93], v[96:97], s[24:25] op_sel_hi:[1,1,0]
	s_nop 0
	v_pk_fma_f32 v[96:97], v[92:93], v[96:97], s[26:27] op_sel_hi:[1,1,0]
	s_nop 0
	v_pk_fma_f32 v[96:97], v[92:93], v[96:97], s[28:29] op_sel_hi:[1,1,0]
	s_nop 0
	v_pk_fma_f32 v[96:97], v[92:93], v[96:97], s[30:31] op_sel_hi:[1,1,0]
	s_nop 0
	v_pk_fma_f32 v[96:97], v[92:93], v[96:97], s[34:35] op_sel_hi:[1,1,0]
	s_nop 0
	v_pk_fma_f32 v[92:93], v[92:93], v[96:97], s[36:37] op_sel_hi:[1,1,0]
	s_nop 0
	v_pk_mul_f32 v[90:91], v[90:91], v[92:93]
	s_nop 0
	v_pk_fma_f32 v[86:87], v[86:87], v[90:91], v[86:87]
	v_pk_mul_f32 v[90:91], v[80:81], s[18:19] op_sel_hi:[1,0]
	v_pk_mul_f32 v[80:81], v[80:81], 0.5 op_sel_hi:[1,0]
	v_med3_f32 v90, v90, s53, v173
	v_med3_f32 v91, v91, s53, v173
	v_pk_mul_f32 v[92:93], v[90:91], v[90:91]
	s_nop 0
	v_pk_fma_f32 v[96:97], v[92:93], s[20:21], v[94:95] op_sel_hi:[1,0,0] neg_lo:[1,0,0] neg_hi:[1,0,0]
	s_nop 0
	v_pk_fma_f32 v[96:97], v[92:93], v[96:97], s[24:25] op_sel_hi:[1,1,0]
	s_nop 0
	v_pk_fma_f32 v[96:97], v[92:93], v[96:97], s[26:27] op_sel_hi:[1,1,0]
	s_nop 0
	v_pk_fma_f32 v[96:97], v[92:93], v[96:97], s[28:29] op_sel_hi:[1,1,0]
	s_nop 0
	v_pk_fma_f32 v[96:97], v[92:93], v[96:97], s[30:31] op_sel_hi:[1,1,0]
	s_nop 0
	v_pk_fma_f32 v[96:97], v[92:93], v[96:97], s[34:35] op_sel_hi:[1,1,0]
	s_nop 0
	v_pk_fma_f32 v[92:93], v[92:93], v[96:97], s[36:37] op_sel_hi:[1,1,0]
	s_nop 0
	v_pk_mul_f32 v[90:91], v[90:91], v[92:93]
	s_nop 0
	v_pk_fma_f32 v[80:81], v[80:81], v[90:91], v[80:81]
	v_pk_mul_f32 v[90:91], v[82:83], s[18:19] op_sel_hi:[1,0]
	v_pk_mul_f32 v[82:83], v[82:83], 0.5 op_sel_hi:[1,0]
	v_med3_f32 v90, v90, s53, v173
	v_med3_f32 v91, v91, s53, v173
	v_pk_mul_f32 v[92:93], v[90:91], v[90:91]
	s_nop 0
	v_pk_fma_f32 v[94:95], v[92:93], s[20:21], v[94:95] op_sel_hi:[1,0,0] neg_lo:[1,0,0] neg_hi:[1,0,0]
	s_nop 0
	v_pk_fma_f32 v[94:95], v[92:93], v[94:95], s[24:25] op_sel_hi:[1,1,0]
	s_nop 0
	v_pk_fma_f32 v[94:95], v[92:93], v[94:95], s[26:27] op_sel_hi:[1,1,0]
	s_nop 0
	v_pk_fma_f32 v[94:95], v[92:93], v[94:95], s[28:29] op_sel_hi:[1,1,0]
	s_nop 0
	v_pk_fma_f32 v[94:95], v[92:93], v[94:95], s[30:31] op_sel_hi:[1,1,0]
	s_nop 0
	v_pk_fma_f32 v[94:95], v[92:93], v[94:95], s[34:35] op_sel_hi:[1,1,0]
	s_nop 0
	v_pk_fma_f32 v[92:93], v[92:93], v[94:95], s[36:37] op_sel_hi:[1,1,0]
	s_nop 0
	v_pk_mul_f32 v[90:91], v[90:91], v[92:93]
	s_nop 0
	v_pk_fma_f32 v[82:83], v[82:83], v[90:91], v[82:83]
; __device__ __forceinline__ unsigned cvt_pk_bf16(float lo, float hi) { unsigned r; asm volatile("v_cvt_pk_bf16_f32 %0, %1, %2" : "=v"(r) : "v"(lo), "v"(hi)); return r; }
; __device__ __forceinline__ f32x2 gelu_pk(f32x2 v) {
;     f32x2 x = v * 0.70710678118f;
;     x.x = __builtin_amdgcn_fmed3f(x.x, -2.9f, 2.9f); x.y = __builtin_amdgcn_fmed3f(x.y, -2.9f, 2.9f);
;     const f32x2 t = x * x;
;     f32x2 p = t * (-4.953124630e-07f) + 1.987094038e-05f;
;     p = p * t + (-3.472001117e-04f); p = p * t + 3.517547622e-03f; p = p * t + (-2.333305031e-02f); p = p * t + 1.087993085e-01f; p = p * t + (-3.740358949e-01f); p = p * t + 1.128076553e+00f;
;     const f32x2 hv = v * 0.5f;
;     return hv * (x * p) + hv;
; }
;     __device__ __forceinline__ void operator()(const f32x4 (&acc)[2][2][4][2], const Unit& u, int wr, int wc, int fr, int fq) const {
;     ...
;             for (int m = 0; m < 4; ++m) { bf16_t* rowp = O + (size_t)(row0 + ai * HALF + m * 16) * ldc + col0;
;                 const float rs = rsqrtf(rsv[ai][m] * (1.f / 1024.f) + 1e-6f);
; #pragma unroll
;                 for (int bj = 0; bj < 2; ++bj) if (bj == 0 || !u.q) { f32x4 v0 = acc[ai][bj][m][0] * rs, v1 = acc[ai][bj][m][1] * rs;
;                     if (act) { f32x2 a = gelu_pk((f32x2){v0[0], v0[1]}), b = gelu_pk((f32x2){v0[2], v0[3]}), c = gelu_pk((f32x2){v1[0], v1[1]}), d = gelu_pk((f32x2){v1[2], v1[3]});
;                         v0 = (f32x4){a.x, a.y, b.x, b.y}; v1 = (f32x4){c.x, c.y, d.x, d.y}; }
;                     u32x4 w; w.x = cvt_pk_bf16(v0[0], v0[1]); w.y = cvt_pk_bf16(v0[2], v0[3]); w.z = cvt_pk_bf16(v1[0], v1[1]); w.w = cvt_pk_bf16(v1[2], v1[3]);
;                     *(u32x4*)(rowp + bj * HALF) = w; } }
.LBB0_2625:
	v_cvt_pk_bf16_f32 v84, v84, v85
	v_cvt_pk_bf16_f32 v85, v86, v87
	v_fmamk_f32 v86, v178, 0x3a800000, v172
	v_mul_f32_e32 v87, 0x4b800000, v86
	v_cmp_gt_f32_e32 vcc, s52, v86
	s_nop 1
	v_cndmask_b32_e32 v86, v86, v87, vcc
	v_rsq_f32_e32 v90, v86
	v_cvt_pk_bf16_f32 v86, v80, v81
	v_cvt_pk_bf16_f32 v87, v82, v83
	global_store_dwordx4 v[88:89], v[84:87], off offset:256 sc1
	v_mul_f32_e32 v80, 0x45800000, v90
	v_cndmask_b32_e32 v80, v90, v80, vcc
	v_pk_mul_f32 v[78:79], v[78:79], v[80:81] op_sel_hi:[1,0]
	v_pk_mul_f32 v[76:77], v[76:77], v[80:81] op_sel_hi:[1,0]
	v_pk_mul_f32 v[74:75], v[74:75], v[80:81] op_sel_hi:[1,0]
	s_and_b64 vcc, exec, s[10:11]
	v_pk_mul_f32 v[82:83], v[72:73], v[80:81] op_sel_hi:[1,0]
	s_cbranch_vccnz .LBB0_2627
	v_pk_mul_f32 v[72:73], v[76:77], s[18:19] op_sel_hi:[1,0]
	v_mov_b64_e32 v[86:87], s[22:23]
	v_med3_f32 v72, v72, s53, v173
	v_med3_f32 v73, v73, s53, v173
	v_pk_mul_f32 v[84:85], v[72:73], v[72:73]
	v_pk_mul_f32 v[76:77], v[76:77], 0.5 op_sel_hi:[1,0]
	v_pk_fma_f32 v[88:89], v[84:85], s[20:21], v[86:87] op_sel_hi:[1,0,0] neg_lo:[1,0,0] neg_hi:[1,0,0]
	s_nop 0
	v_pk_fma_f32 v[88:89], v[84:85], v[88:89], s[24:25] op_sel_hi:[1,1,0]
	s_nop 0
	v_pk_fma_f32 v[88:89], v[84:85], v[88:89], s[26:27] op_sel_hi:[1,1,0]
	s_nop 0
	v_pk_fma_f32 v[88:89], v[84:85], v[88:89], s[28:29] op_sel_hi:[1,1,0]
	s_nop 0
	v_pk_fma_f32 v[88:89], v[84:85], v[88:89], s[30:31] op_sel_hi:[1,1,0]
	s_nop 0
	v_pk_fma_f32 v[88:89], v[84:85], v[88:89], s[34:35] op_sel_hi:[1,1,0]
	s_nop 0
	v_pk_fma_f32 v[84:85], v[84:85], v[88:89], s[36:37] op_sel_hi:[1,1,0]
	s_nop 0
	v_pk_mul_f32 v[72:73], v[72:73], v[84:85]
	s_nop 0
	v_pk_fma_f32 v[76:77], v[76:77], v[72:73], v[76:77]
	v_pk_mul_f32 v[72:73], v[78:79], s[18:19] op_sel_hi:[1,0]
	v_pk_mul_f32 v[78:79], v[78:79], 0.5 op_sel_hi:[1,0]
	v_med3_f32 v72, v72, s53, v173
	v_med3_f32 v73, v73, s53, v173
	v_pk_mul_f32 v[84:85], v[72:73], v[72:73]
	s_nop 0
	v_pk_fma_f32 v[88:89], v[84:85], s[20:21], v[86:87] op_sel_hi:[1,0,0] neg_lo:[1,0,0] neg_hi:[1,0,0]
	s_nop 0
	v_pk_fma_f32 v[88:89], v[84:85], v[88:89], s[24:25] op_sel_hi:[1,1,0]
	s_nop 0
	v_pk_fma_f32 v[88:89], v[84:85], v[88:89], s[26:27] op_sel_hi:[1,1,0]
	s_nop 0
	v_pk_fma_f32 v[88:89], v[84:85], v[88:89], s[28:29] op_sel_hi:[1,1,0]
	s_nop 0
	v_pk_fma_f32 v[88:89], v[84:85], v[88:89], s[30:31] op_sel_hi:[1,1,0]
	s_nop 0
	v_pk_fma_f32 v[88:89], v[84:85], v[88:89], s[34:35] op_sel_hi:[1,1,0]
	s_nop 0
	v_pk_fma_f32 v[84:85], v[84:85], v[88:89], s[36:37] op_sel_hi:[1,1,0]
	s_nop 0
	v_pk_mul_f32 v[72:73], v[72:73], v[84:85]
	s_nop 0
	v_pk_fma_f32 v[78:79], v[78:79], v[72:73], v[78:79]
	v_pk_mul_f32 v[72:73], v[82:83], s[18:19] op_sel_hi:[1,0]
	v_pk_mul_f32 v[82:83], v[82:83], 0.5 op_sel_hi:[1,0]
	v_med3_f32 v72, v72, s53, v173
	v_med3_f32 v73, v73, s53, v173
	v_pk_mul_f32 v[84:85], v[72:73], v[72:73]
	s_nop 0
	v_pk_fma_f32 v[88:89], v[84:85], s[20:21], v[86:87] op_sel_hi:[1,0,0] neg_lo:[1,0,0] neg_hi:[1,0,0]
	s_nop 0
	v_pk_fma_f32 v[88:89], v[84:85], v[88:89], s[24:25] op_sel_hi:[1,1,0]
	s_nop 0
	v_pk_fma_f32 v[88:89], v[84:85], v[88:89], s[26:27] op_sel_hi:[1,1,0]
	s_nop 0
	v_pk_fma_f32 v[88:89], v[84:85], v[88:89], s[28:29] op_sel_hi:[1,1,0]
	s_nop 0
	v_pk_fma_f32 v[88:89], v[84:85], v[88:89], s[30:31] op_sel_hi:[1,1,0]
	s_nop 0
	v_pk_fma_f32 v[88:89], v[84:85], v[88:89], s[34:35] op_sel_hi:[1,1,0]
	s_nop 0
	v_pk_fma_f32 v[84:85], v[84:85], v[88:89], s[36:37] op_sel_hi:[1,1,0]
	s_nop 0
	v_pk_mul_f32 v[72:73], v[72:73], v[84:85]
	s_nop 0
	v_pk_fma_f32 v[82:83], v[82:83], v[72:73], v[82:83]
	v_pk_mul_f32 v[72:73], v[74:75], s[18:19] op_sel_hi:[1,0]
	v_pk_mul_f32 v[74:75], v[74:75], 0.5 op_sel_hi:[1,0]
	v_med3_f32 v72, v72, s53, v173
	v_med3_f32 v73, v73, s53, v173
	v_pk_mul_f32 v[84:85], v[72:73], v[72:73]
	s_nop 0
	v_pk_fma_f32 v[86:87], v[84:85], s[20:21], v[86:87] op_sel_hi:[1,0,0] neg_lo:[1,0,0] neg_hi:[1,0,0]
	s_nop 0
	v_pk_fma_f32 v[86:87], v[84:85], v[86:87], s[24:25] op_sel_hi:[1,1,0]
	s_nop 0
	v_pk_fma_f32 v[86:87], v[84:85], v[86:87], s[26:27] op_sel_hi:[1,1,0]
	s_nop 0
	v_pk_fma_f32 v[86:87], v[84:85], v[86:87], s[28:29] op_sel_hi:[1,1,0]
	s_nop 0
	v_pk_fma_f32 v[86:87], v[84:85], v[86:87], s[30:31] op_sel_hi:[1,1,0]
	s_nop 0
	v_pk_fma_f32 v[86:87], v[84:85], v[86:87], s[34:35] op_sel_hi:[1,1,0]
	s_nop 0
	v_pk_fma_f32 v[84:85], v[84:85], v[86:87], s[36:37] op_sel_hi:[1,1,0]
	s_nop 0
	v_pk_mul_f32 v[72:73], v[72:73], v[84:85]
	s_nop 0
	v_pk_fma_f32 v[74:75], v[74:75], v[72:73], v[74:75]
; __device__ __forceinline__ unsigned cvt_pk_bf16(float lo, float hi) { unsigned r; asm volatile("v_cvt_pk_bf16_f32 %0, %1, %2" : "=v"(r) : "v"(lo), "v"(hi)); return r; }
; __device__ __forceinline__ f32x2 gelu_pk(f32x2 v) {
;     f32x2 x = v * 0.70710678118f;
;     x.x = __builtin_amdgcn_fmed3f(x.x, -2.9f, 2.9f); x.y = __builtin_amdgcn_fmed3f(x.y, -2.9f, 2.9f);
;     const f32x2 t = x * x;
;     f32x2 p = t * (-4.953124630e-07f) + 1.987094038e-05f;
;     p = p * t + (-3.472001117e-04f); p = p * t + 3.517547622e-03f; p = p * t + (-2.333305031e-02f); p = p * t + 1.087993085e-01f; p = p * t + (-3.740358949e-01f); p = p * t + 1.128076553e+00f;
;     const f32x2 hv = v * 0.5f;
;     return hv * (x * p) + hv;
; }
;     __device__ __forceinline__ void operator()(const f32x4 (&acc)[2][2][4][2], const Unit& u, int wr, int wc, int fr, int fq) const {
;     ...
;             for (int m = 0; m < 4; ++m) { bf16_t* rowp = O + (size_t)(row0 + ai * HALF + m * 16) * ldc + col0;
;                 const float rs = rsqrtf(rsv[ai][m] * (1.f / 1024.f) + 1e-6f);
; #pragma unroll
;                 for (int bj = 0; bj < 2; ++bj) if (bj == 0 || !u.q) { f32x4 v0 = acc[ai][bj][m][0] * rs, v1 = acc[ai][bj][m][1] * rs;
;                     if (act) { f32x2 a = gelu_pk((f32x2){v0[0], v0[1]}), b = gelu_pk((f32x2){v0[2], v0[3]}), c = gelu_pk((f32x2){v1[0], v1[1]}), d = gelu_pk((f32x2){v1[2], v1[3]});
;                         v0 = (f32x4){a.x, a.y, b.x, b.y}; v1 = (f32x4){c.x, c.y, d.x, d.y}; }
;                     u32x4 w; w.x = cvt_pk_bf16(v0[0], v0[1]); w.y = cvt_pk_bf16(v0[2], v0[3]); w.z = cvt_pk_bf16(v1[0], v1[1]); w.w = cvt_pk_bf16(v1[2], v1[3]);
;                     *(u32x4*)(rowp + bj * HALF) = w; } }
.LBB0_2627:
	v_lshlrev_b64 v[72:73], 10, v[152:153]
	v_mov_b32_e32 v81, v80
	v_lshl_add_u64 v[72:73], s[64:65], 0, v[72:73]
	v_cvt_pk_bf16_f32 v76, v76, v77
	v_cvt_pk_bf16_f32 v77, v78, v79
	v_cvt_pk_bf16_f32 v78, v82, v83
	v_cvt_pk_bf16_f32 v79, v74, v75
	v_mov_b32_e32 v74, v80
	v_mov_b32_e32 v75, v80
	v_lshl_add_u64 v[72:73], v[120:121], 1, v[72:73]
	v_pk_mul_f32 v[70:71], v[70:71], v[74:75]
	v_pk_mul_f32 v[68:69], v[68:69], v[80:81]
	v_pk_mul_f32 v[66:67], v[66:67], v[74:75]
	s_and_b64 vcc, exec, s[10:11]
	v_pk_mul_f32 v[64:65], v[64:65], v[80:81]
	global_store_dwordx4 v[72:73], v[76:79], off sc1
	s_cbranch_vccnz .LBB0_2629
	v_pk_mul_f32 v[74:75], v[68:69], s[18:19] op_sel_hi:[1,0]
	v_mov_b64_e32 v[78:79], s[22:23]
	v_med3_f32 v74, v74, s53, v173
	v_med3_f32 v75, v75, s53, v173
	v_pk_mul_f32 v[76:77], v[74:75], v[74:75]
	v_pk_mul_f32 v[68:69], v[68:69], 0.5 op_sel_hi:[1,0]
	v_pk_fma_f32 v[80:81], v[76:77], s[20:21], v[78:79] op_sel_hi:[1,0,0] neg_lo:[1,0,0] neg_hi:[1,0,0]
	s_nop 0
	v_pk_fma_f32 v[80:81], v[76:77], v[80:81], s[24:25] op_sel_hi:[1,1,0]
	s_nop 0
	v_pk_fma_f32 v[80:81], v[76:77], v[80:81], s[26:27] op_sel_hi:[1,1,0]
	s_nop 0
	v_pk_fma_f32 v[80:81], v[76:77], v[80:81], s[28:29] op_sel_hi:[1,1,0]
	s_nop 0
	v_pk_fma_f32 v[80:81], v[76:77], v[80:81], s[30:31] op_sel_hi:[1,1,0]
	s_nop 0
	v_pk_fma_f32 v[80:81], v[76:77], v[80:81], s[34:35] op_sel_hi:[1,1,0]
	s_nop 0
	v_pk_fma_f32 v[76:77], v[76:77], v[80:81], s[36:37] op_sel_hi:[1,1,0]
	s_nop 0
	v_pk_mul_f32 v[74:75], v[74:75], v[76:77]
	s_nop 0
	v_pk_fma_f32 v[68:69], v[68:69], v[74:75], v[68:69]
	v_pk_mul_f32 v[74:75], v[70:71], s[18:19] op_sel_hi:[1,0]
	v_pk_mul_f32 v[70:71], v[70:71], 0.5 op_sel_hi:[1,0]
	v_med3_f32 v74, v74, s53, v173
	v_med3_f32 v75, v75, s53, v173
	v_pk_mul_f32 v[76:77], v[74:75], v[74:75]
	s_nop 0
	v_pk_fma_f32 v[80:81], v[76:77], s[20:21], v[78:79] op_sel_hi:[1,0,0] neg_lo:[1,0,0] neg_hi:[1,0,0]
	s_nop 0
	v_pk_fma_f32 v[80:81], v[76:77], v[80:81], s[24:25] op_sel_hi:[1,1,0]
	s_nop 0
	v_pk_fma_f32 v[80:81], v[76:77], v[80:81], s[26:27] op_sel_hi:[1,1,0]
	s_nop 0
	v_pk_fma_f32 v[80:81], v[76:77], v[80:81], s[28:29] op_sel_hi:[1,1,0]
	s_nop 0
	v_pk_fma_f32 v[80:81], v[76:77], v[80:81], s[30:31] op_sel_hi:[1,1,0]
	s_nop 0
	v_pk_fma_f32 v[80:81], v[76:77], v[80:81], s[34:35] op_sel_hi:[1,1,0]
	s_nop 0
	v_pk_fma_f32 v[76:77], v[76:77], v[80:81], s[36:37] op_sel_hi:[1,1,0]
	s_nop 0
	v_pk_mul_f32 v[74:75], v[74:75], v[76:77]
	s_nop 0
	v_pk_fma_f32 v[70:71], v[70:71], v[74:75], v[70:71]
	v_pk_mul_f32 v[74:75], v[64:65], s[18:19] op_sel_hi:[1,0]
	v_pk_mul_f32 v[64:65], v[64:65], 0.5 op_sel_hi:[1,0]
	v_med3_f32 v74, v74, s53, v173
	v_med3_f32 v75, v75, s53, v173
	v_pk_mul_f32 v[76:77], v[74:75], v[74:75]
	s_nop 0
	v_pk_fma_f32 v[80:81], v[76:77], s[20:21], v[78:79] op_sel_hi:[1,0,0] neg_lo:[1,0,0] neg_hi:[1,0,0]
	s_nop 0
	v_pk_fma_f32 v[80:81], v[76:77], v[80:81], s[24:25] op_sel_hi:[1,1,0]
	s_nop 0
	v_pk_fma_f32 v[80:81], v[76:77], v[80:81], s[26:27] op_sel_hi:[1,1,0]
	s_nop 0
	v_pk_fma_f32 v[80:81], v[76:77], v[80:81], s[28:29] op_sel_hi:[1,1,0]
	s_nop 0
	v_pk_fma_f32 v[80:81], v[76:77], v[80:81], s[30:31] op_sel_hi:[1,1,0]
	s_nop 0
	v_pk_fma_f32 v[80:81], v[76:77], v[80:81], s[34:35] op_sel_hi:[1,1,0]
	s_nop 0
	v_pk_fma_f32 v[76:77], v[76:77], v[80:81], s[36:37] op_sel_hi:[1,1,0]
	s_nop 0
	v_pk_mul_f32 v[74:75], v[74:75], v[76:77]
	s_nop 0
	v_pk_fma_f32 v[64:65], v[64:65], v[74:75], v[64:65]
	v_pk_mul_f32 v[74:75], v[66:67], s[18:19] op_sel_hi:[1,0]
	v_pk_mul_f32 v[66:67], v[66:67], 0.5 op_sel_hi:[1,0]
	v_med3_f32 v74, v74, s53, v173
	v_med3_f32 v75, v75, s53, v173
	v_pk_mul_f32 v[76:77], v[74:75], v[74:75]
	s_nop 0
	v_pk_fma_f32 v[78:79], v[76:77], s[20:21], v[78:79] op_sel_hi:[1,0,0] neg_lo:[1,0,0] neg_hi:[1,0,0]
	s_nop 0
	v_pk_fma_f32 v[78:79], v[76:77], v[78:79], s[24:25] op_sel_hi:[1,1,0]
	s_nop 0
	v_pk_fma_f32 v[78:79], v[76:77], v[78:79], s[26:27] op_sel_hi:[1,1,0]
	s_nop 0
	v_pk_fma_f32 v[78:79], v[76:77], v[78:79], s[28:29] op_sel_hi:[1,1,0]
	s_nop 0
	v_pk_fma_f32 v[78:79], v[76:77], v[78:79], s[30:31] op_sel_hi:[1,1,0]
	s_nop 0
	v_pk_fma_f32 v[78:79], v[76:77], v[78:79], s[34:35] op_sel_hi:[1,1,0]
	s_nop 0
	v_pk_fma_f32 v[76:77], v[76:77], v[78:79], s[36:37] op_sel_hi:[1,1,0]
	s_nop 0
	v_pk_mul_f32 v[74:75], v[74:75], v[76:77]
	s_nop 0
	v_pk_fma_f32 v[66:67], v[66:67], v[74:75], v[66:67]
; __device__ __forceinline__ unsigned cvt_pk_bf16(float lo, float hi) { unsigned r; asm volatile("v_cvt_pk_bf16_f32 %0, %1, %2" : "=v"(r) : "v"(lo), "v"(hi)); return r; }
; __device__ __forceinline__ f32x2 gelu_pk(f32x2 v) {
;     f32x2 x = v * 0.70710678118f;
;     x.x = __builtin_amdgcn_fmed3f(x.x, -2.9f, 2.9f); x.y = __builtin_amdgcn_fmed3f(x.y, -2.9f, 2.9f);
;     const f32x2 t = x * x;
;     f32x2 p = t * (-4.953124630e-07f) + 1.987094038e-05f;
;     p = p * t + (-3.472001117e-04f); p = p * t + 3.517547622e-03f; p = p * t + (-2.333305031e-02f); p = p * t + 1.087993085e-01f; p = p * t + (-3.740358949e-01f); p = p * t + 1.128076553e+00f;
;     const f32x2 hv = v * 0.5f;
;     return hv * (x * p) + hv;
; }
;     __device__ __forceinline__ void operator()(const f32x4 (&acc)[2][2][4][2], const Unit& u, int wr, int wc, int fr, int fq) const {
;     ...
;             for (int m = 0; m < 4; ++m) { bf16_t* rowp = O + (size_t)(row0 + ai * HALF + m * 16) * ldc + col0;
;                 const float rs = rsqrtf(rsv[ai][m] * (1.f / 1024.f) + 1e-6f);
; #pragma unroll
;                 for (int bj = 0; bj < 2; ++bj) if (bj == 0 || !u.q) { f32x4 v0 = acc[ai][bj][m][0] * rs, v1 = acc[ai][bj][m][1] * rs;
;                     if (act) { f32x2 a = gelu_pk((f32x2){v0[0], v0[1]}), b = gelu_pk((f32x2){v0[2], v0[3]}), c = gelu_pk((f32x2){v1[0], v1[1]}), d = gelu_pk((f32x2){v1[2], v1[3]});
;                         v0 = (f32x4){a.x, a.y, b.x, b.y}; v1 = (f32x4){c.x, c.y, d.x, d.y}; }
;                     u32x4 w; w.x = cvt_pk_bf16(v0[0], v0[1]); w.y = cvt_pk_bf16(v0[2], v0[3]); w.z = cvt_pk_bf16(v1[0], v1[1]); w.w = cvt_pk_bf16(v1[2], v1[3]);
;                     *(u32x4*)(rowp + bj * HALF) = w; } }
.LBB0_2629:
	v_cvt_pk_bf16_f32 v68, v68, v69
	v_cvt_pk_bf16_f32 v69, v70, v71
	v_fmamk_f32 v70, v177, 0x3a800000, v172
	v_mul_f32_e32 v71, 0x4b800000, v70
	v_cmp_gt_f32_e32 vcc, s52, v70
	s_nop 1
	v_cndmask_b32_e32 v70, v70, v71, vcc
	v_rsq_f32_e32 v74, v70
	v_cvt_pk_bf16_f32 v70, v64, v65
	v_cvt_pk_bf16_f32 v71, v66, v67
	global_store_dwordx4 v[72:73], v[68:71], off offset:256 sc1
	v_mul_f32_e32 v64, 0x45800000, v74
	v_cndmask_b32_e32 v64, v74, v64, vcc
	v_pk_mul_f32 v[62:63], v[62:63], v[64:65] op_sel_hi:[1,0]
	v_pk_mul_f32 v[60:61], v[60:61], v[64:65] op_sel_hi:[1,0]
	v_pk_mul_f32 v[58:59], v[58:59], v[64:65] op_sel_hi:[1,0]
	s_and_b64 vcc, exec, s[10:11]
	v_pk_mul_f32 v[66:67], v[56:57], v[64:65] op_sel_hi:[1,0]
	s_cbranch_vccnz .LBB0_2631
	v_pk_mul_f32 v[56:57], v[60:61], s[18:19] op_sel_hi:[1,0]
	v_mov_b64_e32 v[70:71], s[22:23]
	v_med3_f32 v56, v56, s53, v173
	v_med3_f32 v57, v57, s53, v173
	v_pk_mul_f32 v[68:69], v[56:57], v[56:57]
	v_pk_mul_f32 v[60:61], v[60:61], 0.5 op_sel_hi:[1,0]
	v_pk_fma_f32 v[72:73], v[68:69], s[20:21], v[70:71] op_sel_hi:[1,0,0] neg_lo:[1,0,0] neg_hi:[1,0,0]
	s_nop 0
	v_pk_fma_f32 v[72:73], v[68:69], v[72:73], s[24:25] op_sel_hi:[1,1,0]
	s_nop 0
	v_pk_fma_f32 v[72:73], v[68:69], v[72:73], s[26:27] op_sel_hi:[1,1,0]
	s_nop 0
	v_pk_fma_f32 v[72:73], v[68:69], v[72:73], s[28:29] op_sel_hi:[1,1,0]
	s_nop 0
	v_pk_fma_f32 v[72:73], v[68:69], v[72:73], s[30:31] op_sel_hi:[1,1,0]
	s_nop 0
	v_pk_fma_f32 v[72:73], v[68:69], v[72:73], s[34:35] op_sel_hi:[1,1,0]
	s_nop 0
	v_pk_fma_f32 v[68:69], v[68:69], v[72:73], s[36:37] op_sel_hi:[1,1,0]
	s_nop 0
	v_pk_mul_f32 v[56:57], v[56:57], v[68:69]
	s_nop 0
	v_pk_fma_f32 v[60:61], v[60:61], v[56:57], v[60:61]
	v_pk_mul_f32 v[56:57], v[62:63], s[18:19] op_sel_hi:[1,0]
	v_pk_mul_f32 v[62:63], v[62:63], 0.5 op_sel_hi:[1,0]
	v_med3_f32 v56, v56, s53, v173
	v_med3_f32 v57, v57, s53, v173
	v_pk_mul_f32 v[68:69], v[56:57], v[56:57]
	s_nop 0
	v_pk_fma_f32 v[72:73], v[68:69], s[20:21], v[70:71] op_sel_hi:[1,0,0] neg_lo:[1,0,0] neg_hi:[1,0,0]
	s_nop 0
	v_pk_fma_f32 v[72:73], v[68:69], v[72:73], s[24:25] op_sel_hi:[1,1,0]
	s_nop 0
	v_pk_fma_f32 v[72:73], v[68:69], v[72:73], s[26:27] op_sel_hi:[1,1,0]
	s_nop 0
	v_pk_fma_f32 v[72:73], v[68:69], v[72:73], s[28:29] op_sel_hi:[1,1,0]
	s_nop 0
	v_pk_fma_f32 v[72:73], v[68:69], v[72:73], s[30:31] op_sel_hi:[1,1,0]
	s_nop 0
	v_pk_fma_f32 v[72:73], v[68:69], v[72:73], s[34:35] op_sel_hi:[1,1,0]
	s_nop 0
	v_pk_fma_f32 v[68:69], v[68:69], v[72:73], s[36:37] op_sel_hi:[1,1,0]
	s_nop 0
	v_pk_mul_f32 v[56:57], v[56:57], v[68:69]
	s_nop 0
	v_pk_fma_f32 v[62:63], v[62:63], v[56:57], v[62:63]
	v_pk_mul_f32 v[56:57], v[66:67], s[18:19] op_sel_hi:[1,0]
	v_pk_mul_f32 v[66:67], v[66:67], 0.5 op_sel_hi:[1,0]
	v_med3_f32 v56, v56, s53, v173
	v_med3_f32 v57, v57, s53, v173
	v_pk_mul_f32 v[68:69], v[56:57], v[56:57]
	s_nop 0
	v_pk_fma_f32 v[72:73], v[68:69], s[20:21], v[70:71] op_sel_hi:[1,0,0] neg_lo:[1,0,0] neg_hi:[1,0,0]
	s_nop 0
	v_pk_fma_f32 v[72:73], v[68:69], v[72:73], s[24:25] op_sel_hi:[1,1,0]
	s_nop 0
	v_pk_fma_f32 v[72:73], v[68:69], v[72:73], s[26:27] op_sel_hi:[1,1,0]
	s_nop 0
	v_pk_fma_f32 v[72:73], v[68:69], v[72:73], s[28:29] op_sel_hi:[1,1,0]
	s_nop 0
	v_pk_fma_f32 v[72:73], v[68:69], v[72:73], s[30:31] op_sel_hi:[1,1,0]
	s_nop 0
	v_pk_fma_f32 v[72:73], v[68:69], v[72:73], s[34:35] op_sel_hi:[1,1,0]
	s_nop 0
	v_pk_fma_f32 v[68:69], v[68:69], v[72:73], s[36:37] op_sel_hi:[1,1,0]
	s_nop 0
	v_pk_mul_f32 v[56:57], v[56:57], v[68:69]
	s_nop 0
	v_pk_fma_f32 v[66:67], v[66:67], v[56:57], v[66:67]
	v_pk_mul_f32 v[56:57], v[58:59], s[18:19] op_sel_hi:[1,0]
	v_pk_mul_f32 v[58:59], v[58:59], 0.5 op_sel_hi:[1,0]
	v_med3_f32 v56, v56, s53, v173
	v_med3_f32 v57, v57, s53, v173
	v_pk_mul_f32 v[68:69], v[56:57], v[56:57]
	s_nop 0
	v_pk_fma_f32 v[70:71], v[68:69], s[20:21], v[70:71] op_sel_hi:[1,0,0] neg_lo:[1,0,0] neg_hi:[1,0,0]
	s_nop 0
	v_pk_fma_f32 v[70:71], v[68:69], v[70:71], s[24:25] op_sel_hi:[1,1,0]
	s_nop 0
	v_pk_fma_f32 v[70:71], v[68:69], v[70:71], s[26:27] op_sel_hi:[1,1,0]
	s_nop 0
	v_pk_fma_f32 v[70:71], v[68:69], v[70:71], s[28:29] op_sel_hi:[1,1,0]
	s_nop 0
	v_pk_fma_f32 v[70:71], v[68:69], v[70:71], s[30:31] op_sel_hi:[1,1,0]
	s_nop 0
	v_pk_fma_f32 v[70:71], v[68:69], v[70:71], s[34:35] op_sel_hi:[1,1,0]
	s_nop 0
	v_pk_fma_f32 v[68:69], v[68:69], v[70:71], s[36:37] op_sel_hi:[1,1,0]
	s_nop 0
	v_pk_mul_f32 v[56:57], v[56:57], v[68:69]
	s_nop 0
	v_pk_fma_f32 v[58:59], v[58:59], v[56:57], v[58:59]
; __device__ __forceinline__ unsigned cvt_pk_bf16(float lo, float hi) { unsigned r; asm volatile("v_cvt_pk_bf16_f32 %0, %1, %2" : "=v"(r) : "v"(lo), "v"(hi)); return r; }
; __device__ __forceinline__ f32x2 gelu_pk(f32x2 v) {
;     f32x2 x = v * 0.70710678118f;
;     x.x = __builtin_amdgcn_fmed3f(x.x, -2.9f, 2.9f); x.y = __builtin_amdgcn_fmed3f(x.y, -2.9f, 2.9f);
;     const f32x2 t = x * x;
;     f32x2 p = t * (-4.953124630e-07f) + 1.987094038e-05f;
;     p = p * t + (-3.472001117e-04f); p = p * t + 3.517547622e-03f; p = p * t + (-2.333305031e-02f); p = p * t + 1.087993085e-01f; p = p * t + (-3.740358949e-01f); p = p * t + 1.128076553e+00f;
;     const f32x2 hv = v * 0.5f;
;     return hv * (x * p) + hv;
; }
;     __device__ __forceinline__ void operator()(const f32x4 (&acc)[2][2][4][2], const Unit& u, int wr, int wc, int fr, int fq) const {
;     ...
;             for (int m = 0; m < 4; ++m) { bf16_t* rowp = O + (size_t)(row0 + ai * HALF + m * 16) * ldc + col0;
;                 const float rs = rsqrtf(rsv[ai][m] * (1.f / 1024.f) + 1e-6f);
; #pragma unroll
;                 for (int bj = 0; bj < 2; ++bj) if (bj == 0 || !u.q) { f32x4 v0 = acc[ai][bj][m][0] * rs, v1 = acc[ai][bj][m][1] * rs;
;                     if (act) { f32x2 a = gelu_pk((f32x2){v0[0], v0[1]}), b = gelu_pk((f32x2){v0[2], v0[3]}), c = gelu_pk((f32x2){v1[0], v1[1]}), d = gelu_pk((f32x2){v1[2], v1[3]});
;                         v0 = (f32x4){a.x, a.y, b.x, b.y}; v1 = (f32x4){c.x, c.y, d.x, d.y}; }
;                     u32x4 w; w.x = cvt_pk_bf16(v0[0], v0[1]); w.y = cvt_pk_bf16(v0[2], v0[3]); w.z = cvt_pk_bf16(v1[0], v1[1]); w.w = cvt_pk_bf16(v1[2], v1[3]);
;                     *(u32x4*)(rowp + bj * HALF) = w; } }
.LBB0_2631:
	v_lshlrev_b64 v[56:57], 10, v[150:151]
	v_mov_b32_e32 v65, v64
	v_lshl_add_u64 v[56:57], s[64:65], 0, v[56:57]
	v_cvt_pk_bf16_f32 v60, v60, v61
	v_cvt_pk_bf16_f32 v61, v62, v63
	v_cvt_pk_bf16_f32 v62, v66, v67
	v_cvt_pk_bf16_f32 v63, v58, v59
	v_mov_b32_e32 v58, v64
	v_mov_b32_e32 v59, v64
	v_lshl_add_u64 v[56:57], v[120:121], 1, v[56:57]
	v_pk_mul_f32 v[54:55], v[54:55], v[58:59]
	v_pk_mul_f32 v[52:53], v[52:53], v[64:65]
	v_pk_mul_f32 v[50:51], v[50:51], v[58:59]
	s_and_b64 vcc, exec, s[10:11]
	v_pk_mul_f32 v[48:49], v[48:49], v[64:65]
	global_store_dwordx4 v[56:57], v[60:63], off sc1
	s_cbranch_vccnz .LBB0_2633
	v_pk_mul_f32 v[58:59], v[52:53], s[18:19] op_sel_hi:[1,0]
	v_mov_b64_e32 v[62:63], s[22:23]
	v_med3_f32 v58, v58, s53, v173
	v_med3_f32 v59, v59, s53, v173
	v_pk_mul_f32 v[60:61], v[58:59], v[58:59]
	v_pk_mul_f32 v[52:53], v[52:53], 0.5 op_sel_hi:[1,0]
	v_pk_fma_f32 v[64:65], v[60:61], s[20:21], v[62:63] op_sel_hi:[1,0,0] neg_lo:[1,0,0] neg_hi:[1,0,0]
	s_nop 0
	v_pk_fma_f32 v[64:65], v[60:61], v[64:65], s[24:25] op_sel_hi:[1,1,0]
	s_nop 0
	v_pk_fma_f32 v[64:65], v[60:61], v[64:65], s[26:27] op_sel_hi:[1,1,0]
	s_nop 0
	v_pk_fma_f32 v[64:65], v[60:61], v[64:65], s[28:29] op_sel_hi:[1,1,0]
	s_nop 0
	v_pk_fma_f32 v[64:65], v[60:61], v[64:65], s[30:31] op_sel_hi:[1,1,0]
	s_nop 0
	v_pk_fma_f32 v[64:65], v[60:61], v[64:65], s[34:35] op_sel_hi:[1,1,0]
	s_nop 0
	v_pk_fma_f32 v[60:61], v[60:61], v[64:65], s[36:37] op_sel_hi:[1,1,0]
	s_nop 0
	v_pk_mul_f32 v[58:59], v[58:59], v[60:61]
	s_nop 0
	v_pk_fma_f32 v[52:53], v[52:53], v[58:59], v[52:53]
	v_pk_mul_f32 v[58:59], v[54:55], s[18:19] op_sel_hi:[1,0]
	v_pk_mul_f32 v[54:55], v[54:55], 0.5 op_sel_hi:[1,0]
	v_med3_f32 v58, v58, s53, v173
	v_med3_f32 v59, v59, s53, v173
	v_pk_mul_f32 v[60:61], v[58:59], v[58:59]
	s_nop 0
	v_pk_fma_f32 v[64:65], v[60:61], s[20:21], v[62:63] op_sel_hi:[1,0,0] neg_lo:[1,0,0] neg_hi:[1,0,0]
	s_nop 0
	v_pk_fma_f32 v[64:65], v[60:61], v[64:65], s[24:25] op_sel_hi:[1,1,0]
	s_nop 0
	v_pk_fma_f32 v[64:65], v[60:61], v[64:65], s[26:27] op_sel_hi:[1,1,0]
	s_nop 0
	v_pk_fma_f32 v[64:65], v[60:61], v[64:65], s[28:29] op_sel_hi:[1,1,0]
	s_nop 0
	v_pk_fma_f32 v[64:65], v[60:61], v[64:65], s[30:31] op_sel_hi:[1,1,0]
	s_nop 0
	v_pk_fma_f32 v[64:65], v[60:61], v[64:65], s[34:35] op_sel_hi:[1,1,0]
	s_nop 0
	v_pk_fma_f32 v[60:61], v[60:61], v[64:65], s[36:37] op_sel_hi:[1,1,0]
	s_nop 0
	v_pk_mul_f32 v[58:59], v[58:59], v[60:61]
	s_nop 0
	v_pk_fma_f32 v[54:55], v[54:55], v[58:59], v[54:55]
	v_pk_mul_f32 v[58:59], v[48:49], s[18:19] op_sel_hi:[1,0]
	v_pk_mul_f32 v[48:49], v[48:49], 0.5 op_sel_hi:[1,0]
	v_med3_f32 v58, v58, s53, v173
	v_med3_f32 v59, v59, s53, v173
	v_pk_mul_f32 v[60:61], v[58:59], v[58:59]
	s_nop 0
	v_pk_fma_f32 v[64:65], v[60:61], s[20:21], v[62:63] op_sel_hi:[1,0,0] neg_lo:[1,0,0] neg_hi:[1,0,0]
	s_nop 0
	v_pk_fma_f32 v[64:65], v[60:61], v[64:65], s[24:25] op_sel_hi:[1,1,0]
	s_nop 0
	v_pk_fma_f32 v[64:65], v[60:61], v[64:65], s[26:27] op_sel_hi:[1,1,0]
	s_nop 0
	v_pk_fma_f32 v[64:65], v[60:61], v[64:65], s[28:29] op_sel_hi:[1,1,0]
	s_nop 0
	v_pk_fma_f32 v[64:65], v[60:61], v[64:65], s[30:31] op_sel_hi:[1,1,0]
	s_nop 0
	v_pk_fma_f32 v[64:65], v[60:61], v[64:65], s[34:35] op_sel_hi:[1,1,0]
	s_nop 0
	v_pk_fma_f32 v[60:61], v[60:61], v[64:65], s[36:37] op_sel_hi:[1,1,0]
	s_nop 0
	v_pk_mul_f32 v[58:59], v[58:59], v[60:61]
	s_nop 0
	v_pk_fma_f32 v[48:49], v[48:49], v[58:59], v[48:49]
	v_pk_mul_f32 v[58:59], v[50:51], s[18:19] op_sel_hi:[1,0]
	v_pk_mul_f32 v[50:51], v[50:51], 0.5 op_sel_hi:[1,0]
	v_med3_f32 v58, v58, s53, v173
	v_med3_f32 v59, v59, s53, v173
	v_pk_mul_f32 v[60:61], v[58:59], v[58:59]
	s_nop 0
	v_pk_fma_f32 v[62:63], v[60:61], s[20:21], v[62:63] op_sel_hi:[1,0,0] neg_lo:[1,0,0] neg_hi:[1,0,0]
	s_nop 0
	v_pk_fma_f32 v[62:63], v[60:61], v[62:63], s[24:25] op_sel_hi:[1,1,0]
	s_nop 0
	v_pk_fma_f32 v[62:63], v[60:61], v[62:63], s[26:27] op_sel_hi:[1,1,0]
	s_nop 0
	v_pk_fma_f32 v[62:63], v[60:61], v[62:63], s[28:29] op_sel_hi:[1,1,0]
	s_nop 0
	v_pk_fma_f32 v[62:63], v[60:61], v[62:63], s[30:31] op_sel_hi:[1,1,0]
	s_nop 0
	v_pk_fma_f32 v[62:63], v[60:61], v[62:63], s[34:35] op_sel_hi:[1,1,0]
	s_nop 0
	v_pk_fma_f32 v[60:61], v[60:61], v[62:63], s[36:37] op_sel_hi:[1,1,0]
	s_nop 0
	v_pk_mul_f32 v[58:59], v[58:59], v[60:61]
	s_nop 0
	v_pk_fma_f32 v[50:51], v[50:51], v[58:59], v[50:51]
; __device__ __forceinline__ unsigned cvt_pk_bf16(float lo, float hi) { unsigned r; asm volatile("v_cvt_pk_bf16_f32 %0, %1, %2" : "=v"(r) : "v"(lo), "v"(hi)); return r; }
; __device__ __forceinline__ f32x2 gelu_pk(f32x2 v) {
;     f32x2 x = v * 0.70710678118f;
;     x.x = __builtin_amdgcn_fmed3f(x.x, -2.9f, 2.9f); x.y = __builtin_amdgcn_fmed3f(x.y, -2.9f, 2.9f);
;     const f32x2 t = x * x;
;     f32x2 p = t * (-4.953124630e-07f) + 1.987094038e-05f;
;     p = p * t + (-3.472001117e-04f); p = p * t + 3.517547622e-03f; p = p * t + (-2.333305031e-02f); p = p * t + 1.087993085e-01f; p = p * t + (-3.740358949e-01f); p = p * t + 1.128076553e+00f;
;     const f32x2 hv = v * 0.5f;
;     return hv * (x * p) + hv;
; }
;     __device__ __forceinline__ void operator()(const f32x4 (&acc)[2][2][4][2], const Unit& u, int wr, int wc, int fr, int fq) const {
;     ...
;             for (int m = 0; m < 4; ++m) { bf16_t* rowp = O + (size_t)(row0 + ai * HALF + m * 16) * ldc + col0;
;                 const float rs = rsqrtf(rsv[ai][m] * (1.f / 1024.f) + 1e-6f);
; #pragma unroll
;                 for (int bj = 0; bj < 2; ++bj) if (bj == 0 || !u.q) { f32x4 v0 = acc[ai][bj][m][0] * rs, v1 = acc[ai][bj][m][1] * rs;
;                     if (act) { f32x2 a = gelu_pk((f32x2){v0[0], v0[1]}), b = gelu_pk((f32x2){v0[2], v0[3]}), c = gelu_pk((f32x2){v1[0], v1[1]}), d = gelu_pk((f32x2){v1[2], v1[3]});
;                         v0 = (f32x4){a.x, a.y, b.x, b.y}; v1 = (f32x4){c.x, c.y, d.x, d.y}; }
;                     u32x4 w; w.x = cvt_pk_bf16(v0[0], v0[1]); w.y = cvt_pk_bf16(v0[2], v0[3]); w.z = cvt_pk_bf16(v1[0], v1[1]); w.w = cvt_pk_bf16(v1[2], v1[3]);
;                     *(u32x4*)(rowp + bj * HALF) = w; } }
.LBB0_2633:
	v_cvt_pk_bf16_f32 v52, v52, v53
	v_cvt_pk_bf16_f32 v53, v54, v55
	v_fmamk_f32 v54, v176, 0x3a800000, v172
	v_mul_f32_e32 v55, 0x4b800000, v54
	v_cmp_gt_f32_e32 vcc, s52, v54
	s_nop 1
	v_cndmask_b32_e32 v54, v54, v55, vcc
	v_rsq_f32_e32 v58, v54
	v_cvt_pk_bf16_f32 v54, v48, v49
	v_cvt_pk_bf16_f32 v55, v50, v51
	global_store_dwordx4 v[56:57], v[52:55], off offset:256 sc1
	v_mul_f32_e32 v48, 0x45800000, v58
	v_cndmask_b32_e32 v48, v58, v48, vcc
	v_pk_mul_f32 v[46:47], v[46:47], v[48:49] op_sel_hi:[1,0]
	v_pk_mul_f32 v[44:45], v[44:45], v[48:49] op_sel_hi:[1,0]
	v_pk_mul_f32 v[42:43], v[42:43], v[48:49] op_sel_hi:[1,0]
	s_and_b64 vcc, exec, s[10:11]
	v_pk_mul_f32 v[50:51], v[40:41], v[48:49] op_sel_hi:[1,0]
	s_cbranch_vccnz .LBB0_2635
	v_pk_mul_f32 v[40:41], v[44:45], s[18:19] op_sel_hi:[1,0]
	v_mov_b64_e32 v[54:55], s[22:23]
	v_med3_f32 v40, v40, s53, v173
	v_med3_f32 v41, v41, s53, v173
	v_pk_mul_f32 v[52:53], v[40:41], v[40:41]
	v_pk_mul_f32 v[44:45], v[44:45], 0.5 op_sel_hi:[1,0]
	v_pk_fma_f32 v[56:57], v[52:53], s[20:21], v[54:55] op_sel_hi:[1,0,0] neg_lo:[1,0,0] neg_hi:[1,0,0]
	s_nop 0
	v_pk_fma_f32 v[56:57], v[52:53], v[56:57], s[24:25] op_sel_hi:[1,1,0]
	s_nop 0
	v_pk_fma_f32 v[56:57], v[52:53], v[56:57], s[26:27] op_sel_hi:[1,1,0]
	s_nop 0
	v_pk_fma_f32 v[56:57], v[52:53], v[56:57], s[28:29] op_sel_hi:[1,1,0]
	s_nop 0
	v_pk_fma_f32 v[56:57], v[52:53], v[56:57], s[30:31] op_sel_hi:[1,1,0]
	s_nop 0
	v_pk_fma_f32 v[56:57], v[52:53], v[56:57], s[34:35] op_sel_hi:[1,1,0]
	s_nop 0
	v_pk_fma_f32 v[52:53], v[52:53], v[56:57], s[36:37] op_sel_hi:[1,1,0]
	s_nop 0
	v_pk_mul_f32 v[40:41], v[40:41], v[52:53]
	s_nop 0
	v_pk_fma_f32 v[44:45], v[44:45], v[40:41], v[44:45]
	v_pk_mul_f32 v[40:41], v[46:47], s[18:19] op_sel_hi:[1,0]
	v_pk_mul_f32 v[46:47], v[46:47], 0.5 op_sel_hi:[1,0]
	v_med3_f32 v40, v40, s53, v173
	v_med3_f32 v41, v41, s53, v173
	v_pk_mul_f32 v[52:53], v[40:41], v[40:41]
	s_nop 0
	v_pk_fma_f32 v[56:57], v[52:53], s[20:21], v[54:55] op_sel_hi:[1,0,0] neg_lo:[1,0,0] neg_hi:[1,0,0]
	s_nop 0
	v_pk_fma_f32 v[56:57], v[52:53], v[56:57], s[24:25] op_sel_hi:[1,1,0]
	s_nop 0
	v_pk_fma_f32 v[56:57], v[52:53], v[56:57], s[26:27] op_sel_hi:[1,1,0]
	s_nop 0
	v_pk_fma_f32 v[56:57], v[52:53], v[56:57], s[28:29] op_sel_hi:[1,1,0]
	s_nop 0
	v_pk_fma_f32 v[56:57], v[52:53], v[56:57], s[30:31] op_sel_hi:[1,1,0]
	s_nop 0
	v_pk_fma_f32 v[56:57], v[52:53], v[56:57], s[34:35] op_sel_hi:[1,1,0]
	s_nop 0
	v_pk_fma_f32 v[52:53], v[52:53], v[56:57], s[36:37] op_sel_hi:[1,1,0]
	s_nop 0
	v_pk_mul_f32 v[40:41], v[40:41], v[52:53]
	s_nop 0
	v_pk_fma_f32 v[46:47], v[46:47], v[40:41], v[46:47]
	v_pk_mul_f32 v[40:41], v[50:51], s[18:19] op_sel_hi:[1,0]
	v_pk_mul_f32 v[50:51], v[50:51], 0.5 op_sel_hi:[1,0]
	v_med3_f32 v40, v40, s53, v173
	v_med3_f32 v41, v41, s53, v173
	v_pk_mul_f32 v[52:53], v[40:41], v[40:41]
	s_nop 0
	v_pk_fma_f32 v[56:57], v[52:53], s[20:21], v[54:55] op_sel_hi:[1,0,0] neg_lo:[1,0,0] neg_hi:[1,0,0]
	s_nop 0
	v_pk_fma_f32 v[56:57], v[52:53], v[56:57], s[24:25] op_sel_hi:[1,1,0]
	s_nop 0
	v_pk_fma_f32 v[56:57], v[52:53], v[56:57], s[26:27] op_sel_hi:[1,1,0]
	s_nop 0
	v_pk_fma_f32 v[56:57], v[52:53], v[56:57], s[28:29] op_sel_hi:[1,1,0]
	s_nop 0
	v_pk_fma_f32 v[56:57], v[52:53], v[56:57], s[30:31] op_sel_hi:[1,1,0]
	s_nop 0
	v_pk_fma_f32 v[56:57], v[52:53], v[56:57], s[34:35] op_sel_hi:[1,1,0]
	s_nop 0
	v_pk_fma_f32 v[52:53], v[52:53], v[56:57], s[36:37] op_sel_hi:[1,1,0]
	s_nop 0
	v_pk_mul_f32 v[40:41], v[40:41], v[52:53]
	s_nop 0
	v_pk_fma_f32 v[50:51], v[50:51], v[40:41], v[50:51]
	v_pk_mul_f32 v[40:41], v[42:43], s[18:19] op_sel_hi:[1,0]
	v_pk_mul_f32 v[42:43], v[42:43], 0.5 op_sel_hi:[1,0]
	v_med3_f32 v40, v40, s53, v173
	v_med3_f32 v41, v41, s53, v173
	v_pk_mul_f32 v[52:53], v[40:41], v[40:41]
	s_nop 0
	v_pk_fma_f32 v[54:55], v[52:53], s[20:21], v[54:55] op_sel_hi:[1,0,0] neg_lo:[1,0,0] neg_hi:[1,0,0]
	s_nop 0
	v_pk_fma_f32 v[54:55], v[52:53], v[54:55], s[24:25] op_sel_hi:[1,1,0]
	s_nop 0
	v_pk_fma_f32 v[54:55], v[52:53], v[54:55], s[26:27] op_sel_hi:[1,1,0]
	s_nop 0
	v_pk_fma_f32 v[54:55], v[52:53], v[54:55], s[28:29] op_sel_hi:[1,1,0]
	s_nop 0
	v_pk_fma_f32 v[54:55], v[52:53], v[54:55], s[30:31] op_sel_hi:[1,1,0]
	s_nop 0
	v_pk_fma_f32 v[54:55], v[52:53], v[54:55], s[34:35] op_sel_hi:[1,1,0]
	s_nop 0
	v_pk_fma_f32 v[52:53], v[52:53], v[54:55], s[36:37] op_sel_hi:[1,1,0]
	s_nop 0
	v_pk_mul_f32 v[40:41], v[40:41], v[52:53]
	s_nop 0
	v_pk_fma_f32 v[42:43], v[42:43], v[40:41], v[42:43]
; __device__ __forceinline__ unsigned cvt_pk_bf16(float lo, float hi) { unsigned r; asm volatile("v_cvt_pk_bf16_f32 %0, %1, %2" : "=v"(r) : "v"(lo), "v"(hi)); return r; }
; __device__ __forceinline__ f32x2 gelu_pk(f32x2 v) {
;     f32x2 x = v * 0.70710678118f;
;     x.x = __builtin_amdgcn_fmed3f(x.x, -2.9f, 2.9f); x.y = __builtin_amdgcn_fmed3f(x.y, -2.9f, 2.9f);
;     const f32x2 t = x * x;
;     f32x2 p = t * (-4.953124630e-07f) + 1.987094038e-05f;
;     p = p * t + (-3.472001117e-04f); p = p * t + 3.517547622e-03f; p = p * t + (-2.333305031e-02f); p = p * t + 1.087993085e-01f; p = p * t + (-3.740358949e-01f); p = p * t + 1.128076553e+00f;
;     const f32x2 hv = v * 0.5f;
;     return hv * (x * p) + hv;
; }
;     __device__ __forceinline__ void operator()(const f32x4 (&acc)[2][2][4][2], const Unit& u, int wr, int wc, int fr, int fq) const {
;     ...
;             for (int m = 0; m < 4; ++m) { bf16_t* rowp = O + (size_t)(row0 + ai * HALF + m * 16) * ldc + col0;
;                 const float rs = rsqrtf(rsv[ai][m] * (1.f / 1024.f) + 1e-6f);
; #pragma unroll
;                 for (int bj = 0; bj < 2; ++bj) if (bj == 0 || !u.q) { f32x4 v0 = acc[ai][bj][m][0] * rs, v1 = acc[ai][bj][m][1] * rs;
;                     if (act) { f32x2 a = gelu_pk((f32x2){v0[0], v0[1]}), b = gelu_pk((f32x2){v0[2], v0[3]}), c = gelu_pk((f32x2){v1[0], v1[1]}), d = gelu_pk((f32x2){v1[2], v1[3]});
;                         v0 = (f32x4){a.x, a.y, b.x, b.y}; v1 = (f32x4){c.x, c.y, d.x, d.y}; }
;                     u32x4 w; w.x = cvt_pk_bf16(v0[0], v0[1]); w.y = cvt_pk_bf16(v0[2], v0[3]); w.z = cvt_pk_bf16(v1[0], v1[1]); w.w = cvt_pk_bf16(v1[2], v1[3]);
;                     *(u32x4*)(rowp + bj * HALF) = w; } }
.LBB0_2635:
	v_lshlrev_b64 v[40:41], 10, v[148:149]
	v_mov_b32_e32 v49, v48
	v_lshl_add_u64 v[40:41], s[64:65], 0, v[40:41]
	v_cvt_pk_bf16_f32 v44, v44, v45
	v_cvt_pk_bf16_f32 v45, v46, v47
	v_cvt_pk_bf16_f32 v46, v50, v51
	v_cvt_pk_bf16_f32 v47, v42, v43
	v_mov_b32_e32 v42, v48
	v_mov_b32_e32 v43, v48
	v_lshl_add_u64 v[40:41], v[120:121], 1, v[40:41]
	v_pk_mul_f32 v[38:39], v[38:39], v[42:43]
	v_pk_mul_f32 v[36:37], v[36:37], v[48:49]
	v_pk_mul_f32 v[34:35], v[34:35], v[42:43]
	s_and_b64 vcc, exec, s[10:11]
	v_pk_mul_f32 v[32:33], v[32:33], v[48:49]
	global_store_dwordx4 v[40:41], v[44:47], off sc1
	s_cbranch_vccnz .LBB0_2637
	v_pk_mul_f32 v[42:43], v[36:37], s[18:19] op_sel_hi:[1,0]
	v_mov_b64_e32 v[46:47], s[22:23]
	v_med3_f32 v42, v42, s53, v173
	v_med3_f32 v43, v43, s53, v173
	v_pk_mul_f32 v[44:45], v[42:43], v[42:43]
	v_pk_mul_f32 v[36:37], v[36:37], 0.5 op_sel_hi:[1,0]
	v_pk_fma_f32 v[48:49], v[44:45], s[20:21], v[46:47] op_sel_hi:[1,0,0] neg_lo:[1,0,0] neg_hi:[1,0,0]
	s_nop 0
	v_pk_fma_f32 v[48:49], v[44:45], v[48:49], s[24:25] op_sel_hi:[1,1,0]
	s_nop 0
	v_pk_fma_f32 v[48:49], v[44:45], v[48:49], s[26:27] op_sel_hi:[1,1,0]
	s_nop 0
	v_pk_fma_f32 v[48:49], v[44:45], v[48:49], s[28:29] op_sel_hi:[1,1,0]
	s_nop 0
	v_pk_fma_f32 v[48:49], v[44:45], v[48:49], s[30:31] op_sel_hi:[1,1,0]
	s_nop 0
	v_pk_fma_f32 v[48:49], v[44:45], v[48:49], s[34:35] op_sel_hi:[1,1,0]
	s_nop 0
	v_pk_fma_f32 v[44:45], v[44:45], v[48:49], s[36:37] op_sel_hi:[1,1,0]
	s_nop 0
	v_pk_mul_f32 v[42:43], v[42:43], v[44:45]
	s_nop 0
	v_pk_fma_f32 v[36:37], v[36:37], v[42:43], v[36:37]
	v_pk_mul_f32 v[42:43], v[38:39], s[18:19] op_sel_hi:[1,0]
	v_pk_mul_f32 v[38:39], v[38:39], 0.5 op_sel_hi:[1,0]
	v_med3_f32 v42, v42, s53, v173
	v_med3_f32 v43, v43, s53, v173
	v_pk_mul_f32 v[44:45], v[42:43], v[42:43]
	s_nop 0
	v_pk_fma_f32 v[48:49], v[44:45], s[20:21], v[46:47] op_sel_hi:[1,0,0] neg_lo:[1,0,0] neg_hi:[1,0,0]
	s_nop 0
	v_pk_fma_f32 v[48:49], v[44:45], v[48:49], s[24:25] op_sel_hi:[1,1,0]
	s_nop 0
	v_pk_fma_f32 v[48:49], v[44:45], v[48:49], s[26:27] op_sel_hi:[1,1,0]
	s_nop 0
	v_pk_fma_f32 v[48:49], v[44:45], v[48:49], s[28:29] op_sel_hi:[1,1,0]
	s_nop 0
	v_pk_fma_f32 v[48:49], v[44:45], v[48:49], s[30:31] op_sel_hi:[1,1,0]
	s_nop 0
	v_pk_fma_f32 v[48:49], v[44:45], v[48:49], s[34:35] op_sel_hi:[1,1,0]
	s_nop 0
	v_pk_fma_f32 v[44:45], v[44:45], v[48:49], s[36:37] op_sel_hi:[1,1,0]
	s_nop 0
	v_pk_mul_f32 v[42:43], v[42:43], v[44:45]
	s_nop 0
	v_pk_fma_f32 v[38:39], v[38:39], v[42:43], v[38:39]
	v_pk_mul_f32 v[42:43], v[32:33], s[18:19] op_sel_hi:[1,0]
	v_pk_mul_f32 v[32:33], v[32:33], 0.5 op_sel_hi:[1,0]
	v_med3_f32 v42, v42, s53, v173
	v_med3_f32 v43, v43, s53, v173
	v_pk_mul_f32 v[44:45], v[42:43], v[42:43]
	s_nop 0
	v_pk_fma_f32 v[48:49], v[44:45], s[20:21], v[46:47] op_sel_hi:[1,0,0] neg_lo:[1,0,0] neg_hi:[1,0,0]
	s_nop 0
	v_pk_fma_f32 v[48:49], v[44:45], v[48:49], s[24:25] op_sel_hi:[1,1,0]
	s_nop 0
	v_pk_fma_f32 v[48:49], v[44:45], v[48:49], s[26:27] op_sel_hi:[1,1,0]
	s_nop 0
	v_pk_fma_f32 v[48:49], v[44:45], v[48:49], s[28:29] op_sel_hi:[1,1,0]
	s_nop 0
	v_pk_fma_f32 v[48:49], v[44:45], v[48:49], s[30:31] op_sel_hi:[1,1,0]
	s_nop 0
	v_pk_fma_f32 v[48:49], v[44:45], v[48:49], s[34:35] op_sel_hi:[1,1,0]
	s_nop 0
	v_pk_fma_f32 v[44:45], v[44:45], v[48:49], s[36:37] op_sel_hi:[1,1,0]
	s_nop 0
	v_pk_mul_f32 v[42:43], v[42:43], v[44:45]
	s_nop 0
	v_pk_fma_f32 v[32:33], v[32:33], v[42:43], v[32:33]
	v_pk_mul_f32 v[42:43], v[34:35], s[18:19] op_sel_hi:[1,0]
	v_pk_mul_f32 v[34:35], v[34:35], 0.5 op_sel_hi:[1,0]
	v_med3_f32 v42, v42, s53, v173
	v_med3_f32 v43, v43, s53, v173
	v_pk_mul_f32 v[44:45], v[42:43], v[42:43]
	s_nop 0
	v_pk_fma_f32 v[46:47], v[44:45], s[20:21], v[46:47] op_sel_hi:[1,0,0] neg_lo:[1,0,0] neg_hi:[1,0,0]
	s_nop 0
	v_pk_fma_f32 v[46:47], v[44:45], v[46:47], s[24:25] op_sel_hi:[1,1,0]
	s_nop 0
	v_pk_fma_f32 v[46:47], v[44:45], v[46:47], s[26:27] op_sel_hi:[1,1,0]
	s_nop 0
	v_pk_fma_f32 v[46:47], v[44:45], v[46:47], s[28:29] op_sel_hi:[1,1,0]
	s_nop 0
	v_pk_fma_f32 v[46:47], v[44:45], v[46:47], s[30:31] op_sel_hi:[1,1,0]
	s_nop 0
	v_pk_fma_f32 v[46:47], v[44:45], v[46:47], s[34:35] op_sel_hi:[1,1,0]
	s_nop 0
	v_pk_fma_f32 v[44:45], v[44:45], v[46:47], s[36:37] op_sel_hi:[1,1,0]
	s_nop 0
	v_pk_mul_f32 v[42:43], v[42:43], v[44:45]
	s_nop 0
	v_pk_fma_f32 v[34:35], v[34:35], v[42:43], v[34:35]
; __device__ __forceinline__ unsigned cvt_pk_bf16(float lo, float hi) { unsigned r; asm volatile("v_cvt_pk_bf16_f32 %0, %1, %2" : "=v"(r) : "v"(lo), "v"(hi)); return r; }
; __device__ __forceinline__ f32x2 gelu_pk(f32x2 v) {
;     f32x2 x = v * 0.70710678118f;
;     x.x = __builtin_amdgcn_fmed3f(x.x, -2.9f, 2.9f); x.y = __builtin_amdgcn_fmed3f(x.y, -2.9f, 2.9f);
;     const f32x2 t = x * x;
;     f32x2 p = t * (-4.953124630e-07f) + 1.987094038e-05f;
;     p = p * t + (-3.472001117e-04f); p = p * t + 3.517547622e-03f; p = p * t + (-2.333305031e-02f); p = p * t + 1.087993085e-01f; p = p * t + (-3.740358949e-01f); p = p * t + 1.128076553e+00f;
;     const f32x2 hv = v * 0.5f;
;     return hv * (x * p) + hv;
; }
;     __device__ __forceinline__ void operator()(const f32x4 (&acc)[2][2][4][2], const Unit& u, int wr, int wc, int fr, int fq) const {
;     ...
;             for (int m = 0; m < 4; ++m) { bf16_t* rowp = O + (size_t)(row0 + ai * HALF + m * 16) * ldc + col0;
;                 const float rs = rsqrtf(rsv[ai][m] * (1.f / 1024.f) + 1e-6f);
; #pragma unroll
;                 for (int bj = 0; bj < 2; ++bj) if (bj == 0 || !u.q) { f32x4 v0 = acc[ai][bj][m][0] * rs, v1 = acc[ai][bj][m][1] * rs;
;                     if (act) { f32x2 a = gelu_pk((f32x2){v0[0], v0[1]}), b = gelu_pk((f32x2){v0[2], v0[3]}), c = gelu_pk((f32x2){v1[0], v1[1]}), d = gelu_pk((f32x2){v1[2], v1[3]});
;                         v0 = (f32x4){a.x, a.y, b.x, b.y}; v1 = (f32x4){c.x, c.y, d.x, d.y}; }
;                     u32x4 w; w.x = cvt_pk_bf16(v0[0], v0[1]); w.y = cvt_pk_bf16(v0[2], v0[3]); w.z = cvt_pk_bf16(v1[0], v1[1]); w.w = cvt_pk_bf16(v1[2], v1[3]);
;                     *(u32x4*)(rowp + bj * HALF) = w; } }
.LBB0_2637:
	v_cvt_pk_bf16_f32 v36, v36, v37
	v_cvt_pk_bf16_f32 v37, v38, v39
	v_fmamk_f32 v38, v175, 0x3a800000, v172
	v_mul_f32_e32 v39, 0x4b800000, v38
	v_cmp_gt_f32_e32 vcc, s52, v38
	s_nop 1
	v_cndmask_b32_e32 v38, v38, v39, vcc
	v_rsq_f32_e32 v42, v38
	v_cvt_pk_bf16_f32 v38, v32, v33
	v_cvt_pk_bf16_f32 v39, v34, v35
	global_store_dwordx4 v[40:41], v[36:39], off offset:256 sc1
	v_mul_f32_e32 v32, 0x45800000, v42
	v_cndmask_b32_e32 v32, v42, v32, vcc
	v_pk_mul_f32 v[30:31], v[30:31], v[32:33] op_sel_hi:[1,0]
	v_pk_mul_f32 v[28:29], v[28:29], v[32:33] op_sel_hi:[1,0]
	v_pk_mul_f32 v[26:27], v[26:27], v[32:33] op_sel_hi:[1,0]
	s_and_b64 vcc, exec, s[10:11]
	v_pk_mul_f32 v[34:35], v[24:25], v[32:33] op_sel_hi:[1,0]
	s_cbranch_vccnz .LBB0_2639
	v_pk_mul_f32 v[24:25], v[28:29], s[18:19] op_sel_hi:[1,0]
	v_mov_b64_e32 v[38:39], s[22:23]
	v_med3_f32 v24, v24, s53, v173
	v_med3_f32 v25, v25, s53, v173
	v_pk_mul_f32 v[36:37], v[24:25], v[24:25]
	v_pk_mul_f32 v[28:29], v[28:29], 0.5 op_sel_hi:[1,0]
	v_pk_fma_f32 v[40:41], v[36:37], s[20:21], v[38:39] op_sel_hi:[1,0,0] neg_lo:[1,0,0] neg_hi:[1,0,0]
	s_nop 0
	v_pk_fma_f32 v[40:41], v[36:37], v[40:41], s[24:25] op_sel_hi:[1,1,0]
	s_nop 0
	v_pk_fma_f32 v[40:41], v[36:37], v[40:41], s[26:27] op_sel_hi:[1,1,0]
	s_nop 0
	v_pk_fma_f32 v[40:41], v[36:37], v[40:41], s[28:29] op_sel_hi:[1,1,0]
	s_nop 0
	v_pk_fma_f32 v[40:41], v[36:37], v[40:41], s[30:31] op_sel_hi:[1,1,0]
	s_nop 0
	v_pk_fma_f32 v[40:41], v[36:37], v[40:41], s[34:35] op_sel_hi:[1,1,0]
	s_nop 0
	v_pk_fma_f32 v[36:37], v[36:37], v[40:41], s[36:37] op_sel_hi:[1,1,0]
	s_nop 0
	v_pk_mul_f32 v[24:25], v[24:25], v[36:37]
	s_nop 0
	v_pk_fma_f32 v[28:29], v[28:29], v[24:25], v[28:29]
	v_pk_mul_f32 v[24:25], v[30:31], s[18:19] op_sel_hi:[1,0]
	v_pk_mul_f32 v[30:31], v[30:31], 0.5 op_sel_hi:[1,0]
	v_med3_f32 v24, v24, s53, v173
	v_med3_f32 v25, v25, s53, v173
	v_pk_mul_f32 v[36:37], v[24:25], v[24:25]
	s_nop 0
	v_pk_fma_f32 v[40:41], v[36:37], s[20:21], v[38:39] op_sel_hi:[1,0,0] neg_lo:[1,0,0] neg_hi:[1,0,0]
	s_nop 0
	v_pk_fma_f32 v[40:41], v[36:37], v[40:41], s[24:25] op_sel_hi:[1,1,0]
	s_nop 0
	v_pk_fma_f32 v[40:41], v[36:37], v[40:41], s[26:27] op_sel_hi:[1,1,0]
	s_nop 0
	v_pk_fma_f32 v[40:41], v[36:37], v[40:41], s[28:29] op_sel_hi:[1,1,0]
	s_nop 0
	v_pk_fma_f32 v[40:41], v[36:37], v[40:41], s[30:31] op_sel_hi:[1,1,0]
	s_nop 0
	v_pk_fma_f32 v[40:41], v[36:37], v[40:41], s[34:35] op_sel_hi:[1,1,0]
	s_nop 0
	v_pk_fma_f32 v[36:37], v[36:37], v[40:41], s[36:37] op_sel_hi:[1,1,0]
	s_nop 0
	v_pk_mul_f32 v[24:25], v[24:25], v[36:37]
	s_nop 0
	v_pk_fma_f32 v[30:31], v[30:31], v[24:25], v[30:31]
	v_pk_mul_f32 v[24:25], v[34:35], s[18:19] op_sel_hi:[1,0]
	v_pk_mul_f32 v[34:35], v[34:35], 0.5 op_sel_hi:[1,0]
	v_med3_f32 v24, v24, s53, v173
	v_med3_f32 v25, v25, s53, v173
	v_pk_mul_f32 v[36:37], v[24:25], v[24:25]
	s_nop 0
	v_pk_fma_f32 v[40:41], v[36:37], s[20:21], v[38:39] op_sel_hi:[1,0,0] neg_lo:[1,0,0] neg_hi:[1,0,0]
	s_nop 0
	v_pk_fma_f32 v[40:41], v[36:37], v[40:41], s[24:25] op_sel_hi:[1,1,0]
	s_nop 0
	v_pk_fma_f32 v[40:41], v[36:37], v[40:41], s[26:27] op_sel_hi:[1,1,0]
	s_nop 0
	v_pk_fma_f32 v[40:41], v[36:37], v[40:41], s[28:29] op_sel_hi:[1,1,0]
	s_nop 0
	v_pk_fma_f32 v[40:41], v[36:37], v[40:41], s[30:31] op_sel_hi:[1,1,0]
	s_nop 0
	v_pk_fma_f32 v[40:41], v[36:37], v[40:41], s[34:35] op_sel_hi:[1,1,0]
	s_nop 0
	v_pk_fma_f32 v[36:37], v[36:37], v[40:41], s[36:37] op_sel_hi:[1,1,0]
	s_nop 0
	v_pk_mul_f32 v[24:25], v[24:25], v[36:37]
	s_nop 0
	v_pk_fma_f32 v[34:35], v[34:35], v[24:25], v[34:35]
	v_pk_mul_f32 v[24:25], v[26:27], s[18:19] op_sel_hi:[1,0]
	v_pk_mul_f32 v[26:27], v[26:27], 0.5 op_sel_hi:[1,0]
	v_med3_f32 v24, v24, s53, v173
	v_med3_f32 v25, v25, s53, v173
	v_pk_mul_f32 v[36:37], v[24:25], v[24:25]
	s_nop 0
	v_pk_fma_f32 v[38:39], v[36:37], s[20:21], v[38:39] op_sel_hi:[1,0,0] neg_lo:[1,0,0] neg_hi:[1,0,0]
	s_nop 0
	v_pk_fma_f32 v[38:39], v[36:37], v[38:39], s[24:25] op_sel_hi:[1,1,0]
	s_nop 0
	v_pk_fma_f32 v[38:39], v[36:37], v[38:39], s[26:27] op_sel_hi:[1,1,0]
	s_nop 0
	v_pk_fma_f32 v[38:39], v[36:37], v[38:39], s[28:29] op_sel_hi:[1,1,0]
	s_nop 0
	v_pk_fma_f32 v[38:39], v[36:37], v[38:39], s[30:31] op_sel_hi:[1,1,0]
	s_nop 0
	v_pk_fma_f32 v[38:39], v[36:37], v[38:39], s[34:35] op_sel_hi:[1,1,0]
	s_nop 0
	v_pk_fma_f32 v[36:37], v[36:37], v[38:39], s[36:37] op_sel_hi:[1,1,0]
	s_nop 0
	v_pk_mul_f32 v[24:25], v[24:25], v[36:37]
	s_nop 0
	v_pk_fma_f32 v[26:27], v[26:27], v[24:25], v[26:27]
; __device__ __forceinline__ unsigned cvt_pk_bf16(float lo, float hi) { unsigned r; asm volatile("v_cvt_pk_bf16_f32 %0, %1, %2" : "=v"(r) : "v"(lo), "v"(hi)); return r; }
; __device__ __forceinline__ f32x2 gelu_pk(f32x2 v) {
;     f32x2 x = v * 0.70710678118f;
;     x.x = __builtin_amdgcn_fmed3f(x.x, -2.9f, 2.9f); x.y = __builtin_amdgcn_fmed3f(x.y, -2.9f, 2.9f);
;     const f32x2 t = x * x;
;     f32x2 p = t * (-4.953124630e-07f) + 1.987094038e-05f;
;     p = p * t + (-3.472001117e-04f); p = p * t + 3.517547622e-03f; p = p * t + (-2.333305031e-02f); p = p * t + 1.087993085e-01f; p = p * t + (-3.740358949e-01f); p = p * t + 1.128076553e+00f;
;     const f32x2 hv = v * 0.5f;
;     return hv * (x * p) + hv;
; }
;     __device__ __forceinline__ void operator()(const f32x4 (&acc)[2][2][4][2], const Unit& u, int wr, int wc, int fr, int fq) const {
;     ...
;             for (int m = 0; m < 4; ++m) { bf16_t* rowp = O + (size_t)(row0 + ai * HALF + m * 16) * ldc + col0;
;                 const float rs = rsqrtf(rsv[ai][m] * (1.f / 1024.f) + 1e-6f);
; #pragma unroll
;                 for (int bj = 0; bj < 2; ++bj) if (bj == 0 || !u.q) { f32x4 v0 = acc[ai][bj][m][0] * rs, v1 = acc[ai][bj][m][1] * rs;
;                     if (act) { f32x2 a = gelu_pk((f32x2){v0[0], v0[1]}), b = gelu_pk((f32x2){v0[2], v0[3]}), c = gelu_pk((f32x2){v1[0], v1[1]}), d = gelu_pk((f32x2){v1[2], v1[3]});
;                         v0 = (f32x4){a.x, a.y, b.x, b.y}; v1 = (f32x4){c.x, c.y, d.x, d.y}; }
;                     u32x4 w; w.x = cvt_pk_bf16(v0[0], v0[1]); w.y = cvt_pk_bf16(v0[2], v0[3]); w.z = cvt_pk_bf16(v1[0], v1[1]); w.w = cvt_pk_bf16(v1[2], v1[3]);
;                     *(u32x4*)(rowp + bj * HALF) = w; } }
.LBB0_2639:
	v_lshlrev_b64 v[24:25], 10, v[146:147]
	v_mov_b32_e32 v33, v32
	v_lshl_add_u64 v[24:25], s[64:65], 0, v[24:25]
	v_cvt_pk_bf16_f32 v28, v28, v29
	v_cvt_pk_bf16_f32 v29, v30, v31
	v_cvt_pk_bf16_f32 v30, v34, v35
	v_cvt_pk_bf16_f32 v31, v26, v27
	v_mov_b32_e32 v26, v32
	v_mov_b32_e32 v27, v32
	v_lshl_add_u64 v[24:25], v[120:121], 1, v[24:25]
	v_pk_mul_f32 v[22:23], v[22:23], v[26:27]
	v_pk_mul_f32 v[20:21], v[20:21], v[32:33]
	v_pk_mul_f32 v[18:19], v[18:19], v[26:27]
	s_and_b64 vcc, exec, s[10:11]
	v_pk_mul_f32 v[16:17], v[16:17], v[32:33]
	global_store_dwordx4 v[24:25], v[28:31], off sc1
	s_cbranch_vccnz .LBB0_2641
	v_pk_mul_f32 v[26:27], v[20:21], s[18:19] op_sel_hi:[1,0]
	v_mov_b64_e32 v[30:31], s[22:23]
	v_med3_f32 v26, v26, s53, v173
	v_med3_f32 v27, v27, s53, v173
	v_pk_mul_f32 v[28:29], v[26:27], v[26:27]
	v_pk_mul_f32 v[20:21], v[20:21], 0.5 op_sel_hi:[1,0]
	v_pk_fma_f32 v[32:33], v[28:29], s[20:21], v[30:31] op_sel_hi:[1,0,0] neg_lo:[1,0,0] neg_hi:[1,0,0]
	s_nop 0
	v_pk_fma_f32 v[32:33], v[28:29], v[32:33], s[24:25] op_sel_hi:[1,1,0]
	s_nop 0
	v_pk_fma_f32 v[32:33], v[28:29], v[32:33], s[26:27] op_sel_hi:[1,1,0]
	s_nop 0
	v_pk_fma_f32 v[32:33], v[28:29], v[32:33], s[28:29] op_sel_hi:[1,1,0]
	s_nop 0
	v_pk_fma_f32 v[32:33], v[28:29], v[32:33], s[30:31] op_sel_hi:[1,1,0]
	s_nop 0
	v_pk_fma_f32 v[32:33], v[28:29], v[32:33], s[34:35] op_sel_hi:[1,1,0]
	s_nop 0
	v_pk_fma_f32 v[28:29], v[28:29], v[32:33], s[36:37] op_sel_hi:[1,1,0]
	s_nop 0
	v_pk_mul_f32 v[26:27], v[26:27], v[28:29]
	s_nop 0
	v_pk_fma_f32 v[20:21], v[20:21], v[26:27], v[20:21]
	v_pk_mul_f32 v[26:27], v[22:23], s[18:19] op_sel_hi:[1,0]
	v_pk_mul_f32 v[22:23], v[22:23], 0.5 op_sel_hi:[1,0]
	v_med3_f32 v26, v26, s53, v173
	v_med3_f32 v27, v27, s53, v173
	v_pk_mul_f32 v[28:29], v[26:27], v[26:27]
	s_nop 0
	v_pk_fma_f32 v[32:33], v[28:29], s[20:21], v[30:31] op_sel_hi:[1,0,0] neg_lo:[1,0,0] neg_hi:[1,0,0]
	s_nop 0
	v_pk_fma_f32 v[32:33], v[28:29], v[32:33], s[24:25] op_sel_hi:[1,1,0]
	s_nop 0
	v_pk_fma_f32 v[32:33], v[28:29], v[32:33], s[26:27] op_sel_hi:[1,1,0]
	s_nop 0
	v_pk_fma_f32 v[32:33], v[28:29], v[32:33], s[28:29] op_sel_hi:[1,1,0]
	s_nop 0
	v_pk_fma_f32 v[32:33], v[28:29], v[32:33], s[30:31] op_sel_hi:[1,1,0]
	s_nop 0
	v_pk_fma_f32 v[32:33], v[28:29], v[32:33], s[34:35] op_sel_hi:[1,1,0]
	s_nop 0
	v_pk_fma_f32 v[28:29], v[28:29], v[32:33], s[36:37] op_sel_hi:[1,1,0]
	s_nop 0
	v_pk_mul_f32 v[26:27], v[26:27], v[28:29]
	s_nop 0
	v_pk_fma_f32 v[22:23], v[22:23], v[26:27], v[22:23]
	v_pk_mul_f32 v[26:27], v[16:17], s[18:19] op_sel_hi:[1,0]
	v_pk_mul_f32 v[16:17], v[16:17], 0.5 op_sel_hi:[1,0]
	v_med3_f32 v26, v26, s53, v173
	v_med3_f32 v27, v27, s53, v173
	v_pk_mul_f32 v[28:29], v[26:27], v[26:27]
	s_nop 0
	v_pk_fma_f32 v[32:33], v[28:29], s[20:21], v[30:31] op_sel_hi:[1,0,0] neg_lo:[1,0,0] neg_hi:[1,0,0]
	s_nop 0
	v_pk_fma_f32 v[32:33], v[28:29], v[32:33], s[24:25] op_sel_hi:[1,1,0]
	s_nop 0
	v_pk_fma_f32 v[32:33], v[28:29], v[32:33], s[26:27] op_sel_hi:[1,1,0]
	s_nop 0
	v_pk_fma_f32 v[32:33], v[28:29], v[32:33], s[28:29] op_sel_hi:[1,1,0]
	s_nop 0
	v_pk_fma_f32 v[32:33], v[28:29], v[32:33], s[30:31] op_sel_hi:[1,1,0]
	s_nop 0
	v_pk_fma_f32 v[32:33], v[28:29], v[32:33], s[34:35] op_sel_hi:[1,1,0]
	s_nop 0
	v_pk_fma_f32 v[28:29], v[28:29], v[32:33], s[36:37] op_sel_hi:[1,1,0]
	s_nop 0
	v_pk_mul_f32 v[26:27], v[26:27], v[28:29]
	s_nop 0
	v_pk_fma_f32 v[16:17], v[16:17], v[26:27], v[16:17]
	v_pk_mul_f32 v[26:27], v[18:19], s[18:19] op_sel_hi:[1,0]
	v_pk_mul_f32 v[18:19], v[18:19], 0.5 op_sel_hi:[1,0]
	v_med3_f32 v26, v26, s53, v173
	v_med3_f32 v27, v27, s53, v173
	v_pk_mul_f32 v[28:29], v[26:27], v[26:27]
	s_nop 0
	v_pk_fma_f32 v[30:31], v[28:29], s[20:21], v[30:31] op_sel_hi:[1,0,0] neg_lo:[1,0,0] neg_hi:[1,0,0]
	s_nop 0
	v_pk_fma_f32 v[30:31], v[28:29], v[30:31], s[24:25] op_sel_hi:[1,1,0]
	s_nop 0
	v_pk_fma_f32 v[30:31], v[28:29], v[30:31], s[26:27] op_sel_hi:[1,1,0]
	s_nop 0
	v_pk_fma_f32 v[30:31], v[28:29], v[30:31], s[28:29] op_sel_hi:[1,1,0]
	s_nop 0
	v_pk_fma_f32 v[30:31], v[28:29], v[30:31], s[30:31] op_sel_hi:[1,1,0]
	s_nop 0
	v_pk_fma_f32 v[30:31], v[28:29], v[30:31], s[34:35] op_sel_hi:[1,1,0]
	s_nop 0
	v_pk_fma_f32 v[28:29], v[28:29], v[30:31], s[36:37] op_sel_hi:[1,1,0]
	s_nop 0
	v_pk_mul_f32 v[26:27], v[26:27], v[28:29]
	s_nop 0
	v_pk_fma_f32 v[18:19], v[18:19], v[26:27], v[18:19]
; __device__ __forceinline__ unsigned cvt_pk_bf16(float lo, float hi) { unsigned r; asm volatile("v_cvt_pk_bf16_f32 %0, %1, %2" : "=v"(r) : "v"(lo), "v"(hi)); return r; }
; __device__ __forceinline__ f32x2 gelu_pk(f32x2 v) {
;     f32x2 x = v * 0.70710678118f;
;     x.x = __builtin_amdgcn_fmed3f(x.x, -2.9f, 2.9f); x.y = __builtin_amdgcn_fmed3f(x.y, -2.9f, 2.9f);
;     const f32x2 t = x * x;
;     f32x2 p = t * (-4.953124630e-07f) + 1.987094038e-05f;
;     p = p * t + (-3.472001117e-04f); p = p * t + 3.517547622e-03f; p = p * t + (-2.333305031e-02f); p = p * t + 1.087993085e-01f; p = p * t + (-3.740358949e-01f); p = p * t + 1.128076553e+00f;
;     const f32x2 hv = v * 0.5f;
;     return hv * (x * p) + hv;
; }
;     __device__ __forceinline__ void operator()(const f32x4 (&acc)[2][2][4][2], const Unit& u, int wr, int wc, int fr, int fq) const {
;     ...
;                 const float rs = rsqrtf(rsv[ai][m] * (1.f / 1024.f) + 1e-6f);
; #pragma unroll
;                 for (int bj = 0; bj < 2; ++bj) if (bj == 0 || !u.q) { f32x4 v0 = acc[ai][bj][m][0] * rs, v1 = acc[ai][bj][m][1] * rs;
;                     if (act) { f32x2 a = gelu_pk((f32x2){v0[0], v0[1]}), b = gelu_pk((f32x2){v0[2], v0[3]}), c = gelu_pk((f32x2){v1[0], v1[1]}), d = gelu_pk((f32x2){v1[2], v1[3]});
;                         v0 = (f32x4){a.x, a.y, b.x, b.y}; v1 = (f32x4){c.x, c.y, d.x, d.y}; }
;                     u32x4 w; w.x = cvt_pk_bf16(v0[0], v0[1]); w.y = cvt_pk_bf16(v0[2], v0[3]); w.z = cvt_pk_bf16(v1[0], v1[1]); w.w = cvt_pk_bf16(v1[2], v1[3]);
;                     *(u32x4*)(rowp + bj * HALF) = w; } }
.LBB0_2641:
	v_cvt_pk_bf16_f32 v20, v20, v21
	v_cvt_pk_bf16_f32 v21, v22, v23
	v_fmamk_f32 v22, v174, 0x3a800000, v172
	v_mul_f32_e32 v23, 0x4b800000, v22
	v_cmp_gt_f32_e32 vcc, s52, v22
	s_nop 1
	v_cndmask_b32_e32 v22, v22, v23, vcc
	v_rsq_f32_e32 v26, v22
	v_cvt_pk_bf16_f32 v22, v16, v17
	v_cvt_pk_bf16_f32 v23, v18, v19
	global_store_dwordx4 v[24:25], v[20:23], off offset:256 sc1
	v_mul_f32_e32 v16, 0x45800000, v26
	v_cndmask_b32_e32 v16, v26, v16, vcc
	v_pk_mul_f32 v[14:15], v[14:15], v[16:17] op_sel_hi:[1,0]
	v_pk_mul_f32 v[12:13], v[12:13], v[16:17] op_sel_hi:[1,0]
	v_pk_mul_f32 v[10:11], v[10:11], v[16:17] op_sel_hi:[1,0]
	s_and_b64 vcc, exec, s[10:11]
	v_pk_mul_f32 v[18:19], v[8:9], v[16:17] op_sel_hi:[1,0]
	s_cbranch_vccnz .LBB0_2643
	v_pk_mul_f32 v[8:9], v[12:13], s[18:19] op_sel_hi:[1,0]
	v_mov_b64_e32 v[22:23], s[22:23]
	v_med3_f32 v8, v8, s53, v173
	v_med3_f32 v9, v9, s53, v173
	v_pk_mul_f32 v[20:21], v[8:9], v[8:9]
	v_pk_mul_f32 v[12:13], v[12:13], 0.5 op_sel_hi:[1,0]
	v_pk_fma_f32 v[24:25], v[20:21], s[20:21], v[22:23] op_sel_hi:[1,0,0] neg_lo:[1,0,0] neg_hi:[1,0,0]
	s_nop 0
	v_pk_fma_f32 v[24:25], v[20:21], v[24:25], s[24:25] op_sel_hi:[1,1,0]
	s_nop 0
	v_pk_fma_f32 v[24:25], v[20:21], v[24:25], s[26:27] op_sel_hi:[1,1,0]
	s_nop 0
	v_pk_fma_f32 v[24:25], v[20:21], v[24:25], s[28:29] op_sel_hi:[1,1,0]
	s_nop 0
	v_pk_fma_f32 v[24:25], v[20:21], v[24:25], s[30:31] op_sel_hi:[1,1,0]
	s_nop 0
	v_pk_fma_f32 v[24:25], v[20:21], v[24:25], s[34:35] op_sel_hi:[1,1,0]
	s_nop 0
	v_pk_fma_f32 v[20:21], v[20:21], v[24:25], s[36:37] op_sel_hi:[1,1,0]
	s_nop 0
	v_pk_mul_f32 v[8:9], v[8:9], v[20:21]
	s_nop 0
	v_pk_fma_f32 v[12:13], v[12:13], v[8:9], v[12:13]
	v_pk_mul_f32 v[8:9], v[14:15], s[18:19] op_sel_hi:[1,0]
	v_pk_mul_f32 v[14:15], v[14:15], 0.5 op_sel_hi:[1,0]
	v_med3_f32 v8, v8, s53, v173
	v_med3_f32 v9, v9, s53, v173
	v_pk_mul_f32 v[20:21], v[8:9], v[8:9]
	s_nop 0
	v_pk_fma_f32 v[24:25], v[20:21], s[20:21], v[22:23] op_sel_hi:[1,0,0] neg_lo:[1,0,0] neg_hi:[1,0,0]
	s_nop 0
	v_pk_fma_f32 v[24:25], v[20:21], v[24:25], s[24:25] op_sel_hi:[1,1,0]
	s_nop 0
	v_pk_fma_f32 v[24:25], v[20:21], v[24:25], s[26:27] op_sel_hi:[1,1,0]
	s_nop 0
	v_pk_fma_f32 v[24:25], v[20:21], v[24:25], s[28:29] op_sel_hi:[1,1,0]
	s_nop 0
	v_pk_fma_f32 v[24:25], v[20:21], v[24:25], s[30:31] op_sel_hi:[1,1,0]
	s_nop 0
	v_pk_fma_f32 v[24:25], v[20:21], v[24:25], s[34:35] op_sel_hi:[1,1,0]
	s_nop 0
	v_pk_fma_f32 v[20:21], v[20:21], v[24:25], s[36:37] op_sel_hi:[1,1,0]
	s_nop 0
	v_pk_mul_f32 v[8:9], v[8:9], v[20:21]
	s_nop 0
	v_pk_fma_f32 v[14:15], v[14:15], v[8:9], v[14:15]
	v_pk_mul_f32 v[8:9], v[18:19], s[18:19] op_sel_hi:[1,0]
	v_pk_mul_f32 v[18:19], v[18:19], 0.5 op_sel_hi:[1,0]
	v_med3_f32 v8, v8, s53, v173
	v_med3_f32 v9, v9, s53, v173
	v_pk_mul_f32 v[20:21], v[8:9], v[8:9]
	s_nop 0
	v_pk_fma_f32 v[24:25], v[20:21], s[20:21], v[22:23] op_sel_hi:[1,0,0] neg_lo:[1,0,0] neg_hi:[1,0,0]
	s_nop 0
	v_pk_fma_f32 v[24:25], v[20:21], v[24:25], s[24:25] op_sel_hi:[1,1,0]
	s_nop 0
	v_pk_fma_f32 v[24:25], v[20:21], v[24:25], s[26:27] op_sel_hi:[1,1,0]
	s_nop 0
	v_pk_fma_f32 v[24:25], v[20:21], v[24:25], s[28:29] op_sel_hi:[1,1,0]
	s_nop 0
	v_pk_fma_f32 v[24:25], v[20:21], v[24:25], s[30:31] op_sel_hi:[1,1,0]
	s_nop 0
	v_pk_fma_f32 v[24:25], v[20:21], v[24:25], s[34:35] op_sel_hi:[1,1,0]
	s_nop 0
	v_pk_fma_f32 v[20:21], v[20:21], v[24:25], s[36:37] op_sel_hi:[1,1,0]
	s_nop 0
	v_pk_mul_f32 v[8:9], v[8:9], v[20:21]
	s_nop 0
	v_pk_fma_f32 v[18:19], v[18:19], v[8:9], v[18:19]
	v_pk_mul_f32 v[8:9], v[10:11], s[18:19] op_sel_hi:[1,0]
	v_pk_mul_f32 v[10:11], v[10:11], 0.5 op_sel_hi:[1,0]
	v_med3_f32 v8, v8, s53, v173
	v_med3_f32 v9, v9, s53, v173
	v_pk_mul_f32 v[20:21], v[8:9], v[8:9]
	s_nop 0
	v_pk_fma_f32 v[22:23], v[20:21], s[20:21], v[22:23] op_sel_hi:[1,0,0] neg_lo:[1,0,0] neg_hi:[1,0,0]
	s_nop 0
	v_pk_fma_f32 v[22:23], v[20:21], v[22:23], s[24:25] op_sel_hi:[1,1,0]
	s_nop 0
	v_pk_fma_f32 v[22:23], v[20:21], v[22:23], s[26:27] op_sel_hi:[1,1,0]
	s_nop 0
	v_pk_fma_f32 v[22:23], v[20:21], v[22:23], s[28:29] op_sel_hi:[1,1,0]
	s_nop 0
	v_pk_fma_f32 v[22:23], v[20:21], v[22:23], s[30:31] op_sel_hi:[1,1,0]
	s_nop 0
	v_pk_fma_f32 v[22:23], v[20:21], v[22:23], s[34:35] op_sel_hi:[1,1,0]
	s_nop 0
	v_pk_fma_f32 v[20:21], v[20:21], v[22:23], s[36:37] op_sel_hi:[1,1,0]
	s_nop 0
	v_pk_mul_f32 v[8:9], v[8:9], v[20:21]
	s_nop 0
	v_pk_fma_f32 v[10:11], v[10:11], v[8:9], v[10:11]
; __device__ __forceinline__ unsigned cvt_pk_bf16(float lo, float hi) { unsigned r; asm volatile("v_cvt_pk_bf16_f32 %0, %1, %2" : "=v"(r) : "v"(lo), "v"(hi)); return r; }
; #define PG8_BAR __builtin_amdgcn_s_barrier()
; __device__ __forceinline__ f32x2 gelu_pk(f32x2 v) {
;     f32x2 x = v * 0.70710678118f;
;     x.x = __builtin_amdgcn_fmed3f(x.x, -2.9f, 2.9f); x.y = __builtin_amdgcn_fmed3f(x.y, -2.9f, 2.9f);
;     const f32x2 t = x * x;
;     f32x2 p = t * (-4.953124630e-07f) + 1.987094038e-05f;
;     p = p * t + (-3.472001117e-04f); p = p * t + 3.517547622e-03f; p = p * t + (-2.333305031e-02f); p = p * t + 1.087993085e-01f; p = p * t + (-3.740358949e-01f); p = p * t + 1.128076553e+00f;
;     const f32x2 hv = v * 0.5f;
;     return hv * (x * p) + hv;
; }
;     __device__ __forceinline__ void operator()(const f32x4 (&acc)[2][2][4][2], const Unit& u, int wr, int wc, int fr, int fq) const {
;     ...
;             for (int m = 0; m < 4; ++m) { bf16_t* rowp = O + (size_t)(row0 + ai * HALF + m * 16) * ldc + col0;
;                 const float rs = rsqrtf(rsv[ai][m] * (1.f / 1024.f) + 1e-6f);
; #pragma unroll
;                 for (int bj = 0; bj < 2; ++bj) if (bj == 0 || !u.q) { f32x4 v0 = acc[ai][bj][m][0] * rs, v1 = acc[ai][bj][m][1] * rs;
;                     if (act) { f32x2 a = gelu_pk((f32x2){v0[0], v0[1]}), b = gelu_pk((f32x2){v0[2], v0[3]}), c = gelu_pk((f32x2){v1[0], v1[1]}), d = gelu_pk((f32x2){v1[2], v1[3]});
;                         v0 = (f32x4){a.x, a.y, b.x, b.y}; v1 = (f32x4){c.x, c.y, d.x, d.y}; }
;                     u32x4 w; w.x = cvt_pk_bf16(v0[0], v0[1]); w.y = cvt_pk_bf16(v0[2], v0[3]); w.z = cvt_pk_bf16(v1[0], v1[1]); w.w = cvt_pk_bf16(v1[2], v1[3]);
;                     *(u32x4*)(rowp + bj * HALF) = w; } }
; template <class Epi, class Sched, bool ALIGN_EPI = false, bool SP2 = false>
; __device__ __forceinline__ void gemm_phase(PG8_LAS unsigned char* lds, const Gemm g, const Sched& S, const Epi& E, int wave0) {
;     ...
;         if constexpr (ALIGN_EPI) { if (wr == 1) PG8_BAR; }
.LBB0_2643:
	v_lshlrev_b64 v[8:9], 10, v[144:145]
	v_mov_b32_e32 v17, v16
	v_lshl_add_u64 v[8:9], s[64:65], 0, v[8:9]
	v_cvt_pk_bf16_f32 v12, v12, v13
	v_cvt_pk_bf16_f32 v13, v14, v15
	v_cvt_pk_bf16_f32 v14, v18, v19
	v_cvt_pk_bf16_f32 v15, v10, v11
	v_mov_b32_e32 v10, v16
	v_mov_b32_e32 v11, v16
	v_lshl_add_u64 v[8:9], v[120:121], 1, v[8:9]
	v_pk_mul_f32 v[6:7], v[6:7], v[10:11]
	v_pk_mul_f32 v[4:5], v[4:5], v[16:17]
	v_pk_mul_f32 v[2:3], v[2:3], v[10:11]
	s_and_b64 vcc, exec, s[10:11]
	v_pk_mul_f32 v[0:1], v[0:1], v[16:17]
	global_store_dwordx4 v[8:9], v[12:15], off sc1
	s_cbranch_vccnz .LBB0_2645
	v_pk_mul_f32 v[10:11], v[4:5], s[18:19] op_sel_hi:[1,0]
	v_mov_b64_e32 v[14:15], s[22:23]
	v_med3_f32 v10, v10, s53, v173
	v_med3_f32 v11, v11, s53, v173
	v_pk_mul_f32 v[12:13], v[10:11], v[10:11]
	v_pk_mul_f32 v[4:5], v[4:5], 0.5 op_sel_hi:[1,0]
	v_pk_fma_f32 v[16:17], v[12:13], s[20:21], v[14:15] op_sel_hi:[1,0,0] neg_lo:[1,0,0] neg_hi:[1,0,0]
	s_nop 0
	v_pk_fma_f32 v[16:17], v[12:13], v[16:17], s[24:25] op_sel_hi:[1,1,0]
	s_nop 0
	v_pk_fma_f32 v[16:17], v[12:13], v[16:17], s[26:27] op_sel_hi:[1,1,0]
	s_nop 0
	v_pk_fma_f32 v[16:17], v[12:13], v[16:17], s[28:29] op_sel_hi:[1,1,0]
	s_nop 0
	v_pk_fma_f32 v[16:17], v[12:13], v[16:17], s[30:31] op_sel_hi:[1,1,0]
	s_nop 0
	v_pk_fma_f32 v[16:17], v[12:13], v[16:17], s[34:35] op_sel_hi:[1,1,0]
	s_nop 0
	v_pk_fma_f32 v[12:13], v[12:13], v[16:17], s[36:37] op_sel_hi:[1,1,0]
	s_nop 0
	v_pk_mul_f32 v[10:11], v[10:11], v[12:13]
	s_nop 0
	v_pk_fma_f32 v[4:5], v[4:5], v[10:11], v[4:5]
	v_pk_mul_f32 v[10:11], v[6:7], s[18:19] op_sel_hi:[1,0]
	v_pk_mul_f32 v[6:7], v[6:7], 0.5 op_sel_hi:[1,0]
	v_med3_f32 v10, v10, s53, v173
	v_med3_f32 v11, v11, s53, v173
	v_pk_mul_f32 v[12:13], v[10:11], v[10:11]
	s_nop 0
	v_pk_fma_f32 v[16:17], v[12:13], s[20:21], v[14:15] op_sel_hi:[1,0,0] neg_lo:[1,0,0] neg_hi:[1,0,0]
	s_nop 0
	v_pk_fma_f32 v[16:17], v[12:13], v[16:17], s[24:25] op_sel_hi:[1,1,0]
	s_nop 0
	v_pk_fma_f32 v[16:17], v[12:13], v[16:17], s[26:27] op_sel_hi:[1,1,0]
	s_nop 0
	v_pk_fma_f32 v[16:17], v[12:13], v[16:17], s[28:29] op_sel_hi:[1,1,0]
	s_nop 0
	v_pk_fma_f32 v[16:17], v[12:13], v[16:17], s[30:31] op_sel_hi:[1,1,0]
	s_nop 0
	v_pk_fma_f32 v[16:17], v[12:13], v[16:17], s[34:35] op_sel_hi:[1,1,0]
	s_nop 0
	v_pk_fma_f32 v[12:13], v[12:13], v[16:17], s[36:37] op_sel_hi:[1,1,0]
	s_nop 0
	v_pk_mul_f32 v[10:11], v[10:11], v[12:13]
	s_nop 0
	v_pk_fma_f32 v[6:7], v[6:7], v[10:11], v[6:7]
	v_pk_mul_f32 v[10:11], v[0:1], s[18:19] op_sel_hi:[1,0]
	v_pk_mul_f32 v[0:1], v[0:1], 0.5 op_sel_hi:[1,0]
	v_med3_f32 v10, v10, s53, v173
	v_med3_f32 v11, v11, s53, v173
	v_pk_mul_f32 v[12:13], v[10:11], v[10:11]
	s_nop 0
	v_pk_fma_f32 v[16:17], v[12:13], s[20:21], v[14:15] op_sel_hi:[1,0,0] neg_lo:[1,0,0] neg_hi:[1,0,0]
	s_nop 0
	v_pk_fma_f32 v[16:17], v[12:13], v[16:17], s[24:25] op_sel_hi:[1,1,0]
	s_nop 0
	v_pk_fma_f32 v[16:17], v[12:13], v[16:17], s[26:27] op_sel_hi:[1,1,0]
	s_nop 0
	v_pk_fma_f32 v[16:17], v[12:13], v[16:17], s[28:29] op_sel_hi:[1,1,0]
	s_nop 0
	v_pk_fma_f32 v[16:17], v[12:13], v[16:17], s[30:31] op_sel_hi:[1,1,0]
	s_nop 0
	v_pk_fma_f32 v[16:17], v[12:13], v[16:17], s[34:35] op_sel_hi:[1,1,0]
	s_nop 0
	v_pk_fma_f32 v[12:13], v[12:13], v[16:17], s[36:37] op_sel_hi:[1,1,0]
	s_nop 0
	v_pk_mul_f32 v[10:11], v[10:11], v[12:13]
	s_nop 0
	v_pk_fma_f32 v[0:1], v[0:1], v[10:11], v[0:1]
	v_pk_mul_f32 v[10:11], v[2:3], s[18:19] op_sel_hi:[1,0]
	v_pk_mul_f32 v[2:3], v[2:3], 0.5 op_sel_hi:[1,0]
	v_med3_f32 v10, v10, s53, v173
	v_med3_f32 v11, v11, s53, v173
	v_pk_mul_f32 v[12:13], v[10:11], v[10:11]
	s_nop 0
	v_pk_fma_f32 v[14:15], v[12:13], s[20:21], v[14:15] op_sel_hi:[1,0,0] neg_lo:[1,0,0] neg_hi:[1,0,0]
	s_nop 0
	v_pk_fma_f32 v[14:15], v[12:13], v[14:15], s[24:25] op_sel_hi:[1,1,0]
	s_nop 0
	v_pk_fma_f32 v[14:15], v[12:13], v[14:15], s[26:27] op_sel_hi:[1,1,0]
	s_nop 0
	v_pk_fma_f32 v[14:15], v[12:13], v[14:15], s[28:29] op_sel_hi:[1,1,0]
	s_nop 0
	v_pk_fma_f32 v[14:15], v[12:13], v[14:15], s[30:31] op_sel_hi:[1,1,0]
	s_nop 0
	v_pk_fma_f32 v[14:15], v[12:13], v[14:15], s[34:35] op_sel_hi:[1,1,0]
	s_nop 0
	v_pk_fma_f32 v[12:13], v[12:13], v[14:15], s[36:37] op_sel_hi:[1,1,0]
	s_nop 0
	v_pk_mul_f32 v[10:11], v[10:11], v[12:13]
	s_nop 0
	v_pk_fma_f32 v[2:3], v[2:3], v[10:11], v[2:3]
.LBB0_2645:
	s_andn2_b64 vcc, exec, s[8:9]
	s_mov_b64 s[2:3], -1
	v_cvt_pk_bf16_f32 v4, v4, v5
	v_cvt_pk_bf16_f32 v5, v6, v7
	v_cvt_pk_bf16_f32 v6, v0, v1
	v_cvt_pk_bf16_f32 v7, v2, v3
	global_store_dwordx4 v[8:9], v[4:7], off offset:256 sc1
	s_cbranch_vccnz .LBB0_2602
	s_andn2_b64 vcc, exec, s[6:7]
	s_cbranch_vccnz .LBB0_2601
	s_barrier
	s_branch .LBB0_2601

; __device__ __forceinline__ unsigned cvt_pk_bf16(float lo, float hi) { unsigned r; asm volatile("v_cvt_pk_bf16_f32 %0, %1, %2" : "=v"(r) : "v"(lo), "v"(hi)); return r; }
;     __device__ __forceinline__ void row_out(const f32x4 v0, const f32x4 v1, int row, int col, float& ss) const {
;         if (C) { float* rowp = C + (size_t)row * ldc + col; __builtin_nontemporal_store(v0, (f32x4*)rowp); __builtin_nontemporal_store(v1, (f32x4*)(rowp + 4)); }
;         if (wxb) { u32x4 w; w.x = cvt_pk_bf16(v0[0], v0[1]); w.y = cvt_pk_bf16(v0[2], v0[3]); w.z = cvt_pk_bf16(v1[0], v1[1]); w.w = cvt_pk_bf16(v1[2], v1[3]);
;             *(u32x4*)(XB0 + (size_t)row * ldc + col) = w;
;             ss += (v0[0] * v0[0] + v0[1] * v0[1]) + (v0[2] * v0[2] + v0[3] * v0[3]) + (v1[0] * v1[0] + v1[1] * v1[1]) + (v1[2] * v1[2] + v1[3] * v1[3]); }
;     __device__ __forceinline__ void operator()(const f32x4 (&acc)[2][2][4][2], const Unit& u, int wr, int wc, int fr, int fq) const {
;     ...
;               for (int mh = 0; mh < 4; mh += 2) {
;                 u32x4 rw[2][2];
; #pragma unroll
;                 for (int mm = 0; mm < 2; ++mm) { const int row = row0 + ai * HALF + (mh + mm) * 16;
; #pragma unroll
;                     for (int bj = 0; bj < 2; ++bj) if (bj == 0 || !u.q) rw[mm][bj] = *(const u32x4*)(XB0 + (size_t)row * ldc + col0 + bj * HALF); }
; #pragma unroll
;                 for (int mm = 0; mm < 2; ++mm) { const int m = mh + mm, row = row0 + ai * HALF + m * 16; float ss = 0.f;
; #pragma unroll
;                     for (int bj = 0; bj < 2; ++bj) if (bj == 0 || !u.q) { const u32x4 w = rw[mm][bj];
;                         const f32x4 v0 = acc[ai][bj][m][0] + (f32x4){bf_lo(w.x), bf_hi(w.x), bf_lo(w.y), bf_hi(w.y)}, v1 = acc[ai][bj][m][1] + (f32x4){bf_lo(w.z), bf_hi(w.z), bf_lo(w.w), bf_hi(w.w)};
;                         row_out(v0, v1, row, col0 + bj * HALF, ss); }
;                     if (wxb) { ss += __shfl_xor(ss, 16); ss += __shfl_xor(ss, 32); if (fq == 0) unsafeAtomicAdd(SS + row, ss); } }
.LBB0_2839:
	v_mov_b32_e32 v128, v163
	v_mov_b32_e32 v169, v162
	s_add_i32 s6, s6, s35
	v_and_b32_e32 v183, 64, v168
	v_add_u32_e32 v154, s6, v128
	s_add_i32 s6, s42, s36
	v_lshl_add_u32 v152, v169, 3, s6
	v_ashrrev_i32_e32 v153, 31, v152
	v_lshlrev_b64 v[178:179], 1, v[152:153]
	v_ashrrev_i32_e32 v155, 31, v154
	v_lshl_add_u64 v[156:157], s[96:97], 0, v[178:179]
	v_lshlrev_b64 v[180:181], 11, v[154:155]
	v_lshl_add_u64 v[128:129], v[156:157], 0, v[180:181]
	global_load_dwordx4 v[170:173], v[128:129], off
	global_load_dwordx4 v[174:177], v[128:129], off offset:256
	v_add_u32_e32 v158, 16, v154
	v_ashrrev_i32_e32 v159, 31, v158
	v_lshlrev_b64 v[160:161], 11, v[158:159]
	v_lshl_add_u64 v[128:129], v[156:157], 0, v[160:161]
	global_load_dwordx4 v[132:135], v[128:129], off
	s_nop 0
	global_load_dwordx4 v[128:131], v[128:129], off offset:256
	v_xor_b32_e32 v182, 16, v168
	v_add_u32_e32 v183, 64, v183
	v_xor_b32_e32 v184, 32, v168
	v_cmp_lt_i32_e64 s[6:7], v182, v183
	v_cmp_eq_u32_e32 vcc, 0, v169
	v_lshl_add_u64 v[180:181], s[96:97], 0, v[180:181]
	v_cndmask_b32_e64 v169, v168, v182, s[6:7]
	v_cmp_lt_i32_e64 s[6:7], v184, v183
	v_lshl_add_u64 v[178:179], v[180:181], 0, v[178:179]
	v_lshlrev_b32_e32 v169, 2, v169
	v_cndmask_b32_e64 v188, v168, v184, s[6:7]
	s_waitcnt vmcnt(0)
	v_lshlrev_b32_e32 v180, 16, v170
	v_and_b32_e32 v181, 0xffff0000, v170
	v_lshlrev_b32_e32 v170, 16, v171
	v_and_b32_e32 v171, 0xffff0000, v171
	v_lshlrev_b32_e32 v184, 16, v174
	v_and_b32_e32 v185, 0xffff0000, v174
	v_lshlrev_b32_e32 v174, 16, v175
	v_and_b32_e32 v175, 0xffff0000, v175
	v_lshlrev_b32_e32 v182, 16, v172
	v_and_b32_e32 v183, 0xffff0000, v172
	v_lshlrev_b32_e32 v172, 16, v173
	v_and_b32_e32 v173, 0xffff0000, v173
	v_lshlrev_b32_e32 v186, 16, v176
	v_and_b32_e32 v187, 0xffff0000, v176
	v_lshlrev_b32_e32 v176, 16, v177
	v_and_b32_e32 v177, 0xffff0000, v177
	v_pk_add_f32 v[126:127], v[126:127], v[170:171]
	v_pk_add_f32 v[124:125], v[124:125], v[180:181]
	v_pk_add_f32 v[118:119], v[118:119], v[174:175]
	v_pk_add_f32 v[116:117], v[116:117], v[184:185]
	v_pk_add_f32 v[122:123], v[122:123], v[172:173]
	v_pk_add_f32 v[120:121], v[120:121], v[182:183]
	v_pk_add_f32 v[170:171], v[114:115], v[176:177]
	v_pk_add_f32 v[172:173], v[112:113], v[186:187]
	v_mul_f32_e32 v114, v125, v125
	v_mul_f32_e32 v115, v127, v127
	v_mul_f32_e32 v176, v117, v117
	v_mul_f32_e32 v177, v119, v119
	v_cvt_pk_bf16_f32 v112, v124, v125
	v_mul_f32_e32 v125, v121, v121
	v_mul_f32_e32 v175, v173, v173
	v_fmac_f32_e32 v114, v124, v124
	v_fmac_f32_e32 v115, v126, v126
	v_fmac_f32_e32 v176, v116, v116
	v_fmac_f32_e32 v177, v118, v118
	v_cvt_pk_bf16_f32 v113, v126, v127
	v_mul_f32_e32 v127, v123, v123
	v_mul_f32_e32 v174, v171, v171
	v_fmac_f32_e32 v125, v120, v120
	v_fmac_f32_e32 v175, v172, v172
	v_add_f32_e32 v114, v114, v115
	v_add_f32_e32 v115, v176, v177
	v_fmac_f32_e32 v127, v122, v122
	v_fmac_f32_e32 v174, v170, v170
	v_add_f32_e32 v114, v125, v114
	v_add_f32_e32 v115, v175, v115
	v_add_f32_e32 v114, v127, v114
	v_add_f32_e32 v115, v174, v115
	v_add_f32_e32 v124, v114, v115
	ds_bpermute_b32 v125, v169, v124
	v_cvt_pk_bf16_f32 v114, v120, v121
	v_cvt_pk_bf16_f32 v115, v122, v123
	global_store_dwordx4 v[178:179], v[112:115], off sc1
	v_cvt_pk_bf16_f32 v116, v116, v117
	v_cvt_pk_bf16_f32 v117, v118, v119
	v_cvt_pk_bf16_f32 v118, v172, v173
	v_cvt_pk_bf16_f32 v119, v170, v171
	global_store_dwordx4 v[178:179], v[116:119], off offset:256 sc1
	s_waitcnt lgkmcnt(0)
	v_add_f32_e32 v113, v124, v125
	v_lshlrev_b32_e32 v112, 2, v188
	ds_bpermute_b32 v114, v112, v113
	s_and_saveexec_b64 s[6:7], vcc
	s_cbranch_execz .LBB0_2841
	s_waitcnt lgkmcnt(0)
	v_add_f32_e32 v113, v113, v114
	v_lshl_add_u64 v[114:115], v[154:155], 2, s[10:11]
	global_atomic_add_f32 v[114:115], v113, off
.LBB0_2841:
	s_or_b64 exec, exec, s[6:7]
	s_waitcnt lgkmcnt(0)
	v_lshlrev_b32_e32 v114, 16, v132
	v_and_b32_e32 v115, 0xffff0000, v132
	v_lshlrev_b32_e32 v116, 16, v133
	v_and_b32_e32 v117, 0xffff0000, v133
	v_pk_add_f32 v[108:109], v[108:109], v[114:115]
	v_lshlrev_b32_e32 v114, 16, v134
	v_and_b32_e32 v115, 0xffff0000, v134
	v_pk_add_f32 v[110:111], v[110:111], v[116:117]
	v_pk_add_f32 v[114:115], v[104:105], v[114:115]
	v_cvt_pk_bf16_f32 v104, v108, v109
	v_mul_f32_e32 v109, v109, v109
	v_fmac_f32_e32 v109, v108, v108
	v_mul_f32_e32 v108, v111, v111
	v_fmac_f32_e32 v108, v110, v110
	v_lshlrev_b32_e32 v116, 16, v135
	v_and_b32_e32 v117, 0xffff0000, v135
	v_add_f32_e32 v108, v109, v108
	v_mul_f32_e32 v109, v115, v115
	v_pk_add_f32 v[116:117], v[106:107], v[116:117]
	v_fmac_f32_e32 v109, v114, v114
	v_add_f32_e32 v108, v109, v108
	v_mul_f32_e32 v109, v117, v117
	v_fmac_f32_e32 v109, v116, v116
	v_cvt_pk_bf16_f32 v105, v110, v111
	v_add_f32_e32 v113, v109, v108
	v_lshlrev_b32_e32 v108, 16, v128
	v_and_b32_e32 v109, 0xffff0000, v128
	v_lshlrev_b32_e32 v110, 16, v129
	v_and_b32_e32 v111, 0xffff0000, v129
	v_pk_add_f32 v[102:103], v[102:103], v[110:111]
	v_pk_add_f32 v[100:101], v[100:101], v[108:109]
	v_lshlrev_b32_e32 v108, 16, v130
	v_and_b32_e32 v109, 0xffff0000, v130
	v_lshlrev_b32_e32 v110, 16, v131
	v_and_b32_e32 v111, 0xffff0000, v131
	v_pk_add_f32 v[110:111], v[98:99], v[110:111]
	v_pk_add_f32 v[108:109], v[96:97], v[108:109]
	v_mul_f32_e32 v98, v101, v101
	v_mul_f32_e32 v99, v103, v103
	v_mul_f32_e32 v97, v109, v109
	v_fmac_f32_e32 v98, v100, v100
	v_fmac_f32_e32 v99, v102, v102
	v_mul_f32_e32 v96, v111, v111
	v_fmac_f32_e32 v97, v108, v108
	v_add_f32_e32 v98, v98, v99
	v_fmac_f32_e32 v96, v110, v110
	v_add_f32_e32 v97, v97, v98
	v_add_f32_e32 v96, v96, v97
	v_add_f32_e32 v99, v113, v96
	ds_bpermute_b32 v113, v169, v99
	v_lshl_add_u64 v[96:97], s[96:97], 0, v[160:161]
	v_cvt_pk_bf16_f32 v106, v114, v115
	v_lshl_add_u64 v[114:115], v[152:153], 1, v[96:97]
	v_cvt_pk_bf16_f32 v107, v116, v117
	s_waitcnt lgkmcnt(0)
	v_add_f32_e32 v96, v99, v113
	ds_bpermute_b32 v97, v112, v96
	global_store_dwordx4 v[114:115], v[104:107], off sc1
	v_cvt_pk_bf16_f32 v98, v100, v101
	v_cvt_pk_bf16_f32 v99, v102, v103
	v_cvt_pk_bf16_f32 v100, v108, v109
	v_cvt_pk_bf16_f32 v101, v110, v111
	global_store_dwordx4 v[114:115], v[98:101], off offset:256 sc1
	s_and_saveexec_b64 s[6:7], vcc
	s_cbranch_execz .LBB0_2843
	s_waitcnt lgkmcnt(0)
	v_add_f32_e32 v98, v96, v97
	v_lshl_add_u64 v[96:97], v[158:159], 2, s[10:11]
	global_atomic_add_f32 v[96:97], v98, off
; __device__ __forceinline__ unsigned cvt_pk_bf16(float lo, float hi) { unsigned r; asm volatile("v_cvt_pk_bf16_f32 %0, %1, %2" : "=v"(r) : "v"(lo), "v"(hi)); return r; }
;     __device__ __forceinline__ void row_out(const f32x4 v0, const f32x4 v1, int row, int col, float& ss) const {
;         if (C) { float* rowp = C + (size_t)row * ldc + col; __builtin_nontemporal_store(v0, (f32x4*)rowp); __builtin_nontemporal_store(v1, (f32x4*)(rowp + 4)); }
;         if (wxb) { u32x4 w; w.x = cvt_pk_bf16(v0[0], v0[1]); w.y = cvt_pk_bf16(v0[2], v0[3]); w.z = cvt_pk_bf16(v1[0], v1[1]); w.w = cvt_pk_bf16(v1[2], v1[3]);
;             *(u32x4*)(XB0 + (size_t)row * ldc + col) = w;
;             ss += (v0[0] * v0[0] + v0[1] * v0[1]) + (v0[2] * v0[2] + v0[3] * v0[3]) + (v1[0] * v1[0] + v1[1] * v1[1]) + (v1[2] * v1[2] + v1[3] * v1[3]); }
;     __device__ __forceinline__ void operator()(const f32x4 (&acc)[2][2][4][2], const Unit& u, int wr, int wc, int fr, int fq) const {
;     ...
;               for (int mh = 0; mh < 4; mh += 2) {
;                 u32x4 rw[2][2];
; #pragma unroll
;                 for (int mm = 0; mm < 2; ++mm) { const int row = row0 + ai * HALF + (mh + mm) * 16;
; #pragma unroll
;                     for (int bj = 0; bj < 2; ++bj) if (bj == 0 || !u.q) rw[mm][bj] = *(const u32x4*)(XB0 + (size_t)row * ldc + col0 + bj * HALF); }
; #pragma unroll
;                 for (int mm = 0; mm < 2; ++mm) { const int m = mh + mm, row = row0 + ai * HALF + m * 16; float ss = 0.f;
; #pragma unroll
;                     for (int bj = 0; bj < 2; ++bj) if (bj == 0 || !u.q) { const u32x4 w = rw[mm][bj];
;                         const f32x4 v0 = acc[ai][bj][m][0] + (f32x4){bf_lo(w.x), bf_hi(w.x), bf_lo(w.y), bf_hi(w.y)}, v1 = acc[ai][bj][m][1] + (f32x4){bf_lo(w.z), bf_hi(w.z), bf_lo(w.w), bf_hi(w.w)};
;                         row_out(v0, v1, row, col0 + bj * HALF, ss); }
;                     if (wxb) { ss += __shfl_xor(ss, 16); ss += __shfl_xor(ss, 32); if (fq == 0) unsafeAtomicAdd(SS + row, ss); } }
.LBB0_2843:
	s_or_b64 exec, exec, s[6:7]
	v_add_u32_e32 v108, 32, v154
	v_ashrrev_i32_e32 v109, 31, v108
	v_lshlrev_b64 v[110:111], 11, v[108:109]
	s_waitcnt lgkmcnt(0)
	v_lshl_add_u64 v[96:97], v[156:157], 0, v[110:111]
	global_load_dwordx4 v[114:117], v[96:97], off
	global_load_dwordx4 v[118:121], v[96:97], off offset:256
	v_add_u32_e32 v104, 48, v154
	v_ashrrev_i32_e32 v105, 31, v104
	v_lshlrev_b64 v[106:107], 11, v[104:105]
	v_lshl_add_u64 v[96:97], v[156:157], 0, v[106:107]
	global_load_dwordx4 v[100:103], v[96:97], off
	s_nop 0
	global_load_dwordx4 v[96:99], v[96:97], off offset:256
	s_waitcnt vmcnt(3)
	v_lshlrev_b32_e32 v122, 16, v114
	v_and_b32_e32 v123, 0xffff0000, v114
	v_lshlrev_b32_e32 v114, 16, v115
	v_and_b32_e32 v115, 0xffff0000, v115
	s_waitcnt vmcnt(2)
	v_lshlrev_b32_e32 v126, 16, v118
	v_and_b32_e32 v127, 0xffff0000, v118
	v_lshlrev_b32_e32 v118, 16, v119
	v_and_b32_e32 v119, 0xffff0000, v119
	v_lshlrev_b32_e32 v124, 16, v116
	v_and_b32_e32 v125, 0xffff0000, v116
	v_lshlrev_b32_e32 v116, 16, v117
	v_and_b32_e32 v117, 0xffff0000, v117
	v_lshlrev_b32_e32 v128, 16, v120
	v_and_b32_e32 v129, 0xffff0000, v120
	v_lshlrev_b32_e32 v120, 16, v121
	v_and_b32_e32 v121, 0xffff0000, v121
	v_pk_add_f32 v[94:95], v[94:95], v[114:115]
	v_pk_add_f32 v[92:93], v[92:93], v[122:123]
	v_pk_add_f32 v[86:87], v[86:87], v[118:119]
	v_pk_add_f32 v[84:85], v[84:85], v[126:127]
	v_pk_add_f32 v[90:91], v[90:91], v[116:117]
	v_pk_add_f32 v[88:89], v[88:89], v[124:125]
	v_pk_add_f32 v[114:115], v[82:83], v[120:121]
	v_pk_add_f32 v[116:117], v[80:81], v[128:129]
	v_cvt_pk_bf16_f32 v80, v92, v93
	v_cvt_pk_bf16_f32 v81, v94, v95
	v_mul_f32_e32 v93, v93, v93
	v_mul_f32_e32 v95, v95, v95
	v_mul_f32_e32 v119, v85, v85
	v_mul_f32_e32 v120, v87, v87
	v_cvt_pk_bf16_f32 v82, v88, v89
	v_cvt_pk_bf16_f32 v83, v90, v91
	v_mul_f32_e32 v89, v89, v89
	v_mul_f32_e32 v91, v91, v91
	v_mul_f32_e32 v118, v117, v117
	v_fmac_f32_e32 v93, v92, v92
	v_fmac_f32_e32 v95, v94, v94
	v_fmac_f32_e32 v119, v84, v84
	v_fmac_f32_e32 v120, v86, v86
	v_mul_f32_e32 v113, v115, v115
	v_fmac_f32_e32 v89, v88, v88
	v_fmac_f32_e32 v91, v90, v90
	v_fmac_f32_e32 v118, v116, v116
	v_add_f32_e32 v88, v93, v95
	v_add_f32_e32 v90, v119, v120
	v_fmac_f32_e32 v113, v114, v114
	v_add_f32_e32 v88, v89, v88
	v_add_f32_e32 v89, v118, v90
	v_add_f32_e32 v88, v91, v88
	v_add_f32_e32 v89, v113, v89
	v_add_f32_e32 v90, v88, v89
	ds_bpermute_b32 v91, v169, v90
	v_lshl_add_u64 v[88:89], s[96:97], 0, v[110:111]
	v_lshl_add_u64 v[88:89], v[152:153], 1, v[88:89]
	global_store_dwordx4 v[88:89], v[80:83], off sc1
	s_waitcnt lgkmcnt(0)
	s_nop 0
	v_add_f32_e32 v80, v90, v91
	ds_bpermute_b32 v81, v112, v80
	v_cvt_pk_bf16_f32 v82, v84, v85
	v_cvt_pk_bf16_f32 v83, v86, v87
	v_cvt_pk_bf16_f32 v84, v116, v117
	v_cvt_pk_bf16_f32 v85, v114, v115
	global_store_dwordx4 v[88:89], v[82:85], off offset:256 sc1
	s_and_saveexec_b64 s[6:7], vcc
	s_cbranch_execz .LBB0_2845
	s_waitcnt lgkmcnt(0)
	v_add_f32_e32 v82, v80, v81
	v_lshl_add_u64 v[80:81], v[108:109], 2, s[10:11]
	global_atomic_add_f32 v[80:81], v82, off
.LBB0_2845:
	s_or_b64 exec, exec, s[6:7]
	s_waitcnt vmcnt(3)
	v_lshlrev_b32_e32 v80, 16, v100
	s_waitcnt lgkmcnt(0)
	v_and_b32_e32 v81, 0xffff0000, v100
	v_lshlrev_b32_e32 v82, 16, v101
	v_and_b32_e32 v83, 0xffff0000, v101
	v_pk_add_f32 v[76:77], v[76:77], v[80:81]
	v_lshlrev_b32_e32 v80, 16, v102
	v_and_b32_e32 v81, 0xffff0000, v102
	v_pk_add_f32 v[78:79], v[78:79], v[82:83]
	v_pk_add_f32 v[80:81], v[72:73], v[80:81]
	v_cvt_pk_bf16_f32 v72, v76, v77
	v_mul_f32_e32 v77, v77, v77
	v_fmac_f32_e32 v77, v76, v76
	v_mul_f32_e32 v76, v79, v79
	v_fmac_f32_e32 v76, v78, v78
	v_lshlrev_b32_e32 v82, 16, v103
	v_and_b32_e32 v83, 0xffff0000, v103
	v_add_f32_e32 v76, v77, v76
	v_mul_f32_e32 v77, v81, v81
	v_pk_add_f32 v[82:83], v[74:75], v[82:83]
	v_fmac_f32_e32 v77, v80, v80
	v_add_f32_e32 v76, v77, v76
	v_mul_f32_e32 v77, v83, v83
	v_fmac_f32_e32 v77, v82, v82
	v_cvt_pk_bf16_f32 v73, v78, v79
	v_cvt_pk_bf16_f32 v74, v80, v81
	v_add_f32_e32 v80, v77, v76
	s_waitcnt vmcnt(2)
	v_lshlrev_b32_e32 v76, 16, v96
	v_and_b32_e32 v77, 0xffff0000, v96
	v_lshlrev_b32_e32 v78, 16, v97
	v_and_b32_e32 v79, 0xffff0000, v97
	v_pk_add_f32 v[70:71], v[70:71], v[78:79]
	v_pk_add_f32 v[68:69], v[68:69], v[76:77]
	v_lshlrev_b32_e32 v76, 16, v98
	v_and_b32_e32 v77, 0xffff0000, v98
	v_lshlrev_b32_e32 v78, 16, v99
	v_and_b32_e32 v79, 0xffff0000, v99
	v_pk_add_f32 v[78:79], v[66:67], v[78:79]
	v_pk_add_f32 v[76:77], v[64:65], v[76:77]
	v_mul_f32_e32 v66, v69, v69
	v_mul_f32_e32 v67, v71, v71
	v_mul_f32_e32 v65, v77, v77
	v_fmac_f32_e32 v66, v68, v68
	v_fmac_f32_e32 v67, v70, v70
	v_mul_f32_e32 v64, v79, v79
	v_fmac_f32_e32 v65, v76, v76
	v_add_f32_e32 v66, v66, v67
	v_fmac_f32_e32 v64, v78, v78
	v_add_f32_e32 v65, v65, v66
	v_add_f32_e32 v64, v64, v65
	v_add_f32_e32 v67, v80, v64
	v_cvt_pk_bf16_f32 v75, v82, v83
	ds_bpermute_b32 v82, v169, v67
	v_lshl_add_u64 v[64:65], s[96:97], 0, v[106:107]
	v_lshl_add_u64 v[80:81], v[152:153], 1, v[64:65]
	global_store_dwordx4 v[80:81], v[72:75], off sc1
	v_cvt_pk_bf16_f32 v66, v68, v69
	s_waitcnt lgkmcnt(0)
	v_add_f32_e32 v64, v67, v82
	ds_bpermute_b32 v65, v112, v64
	v_cvt_pk_bf16_f32 v67, v70, v71
	v_cvt_pk_bf16_f32 v68, v76, v77
	v_cvt_pk_bf16_f32 v69, v78, v79
	global_store_dwordx4 v[80:81], v[66:69], off offset:256 sc1
	s_and_saveexec_b64 s[6:7], vcc
	s_cbranch_execz .LBB0_2847
	s_waitcnt lgkmcnt(0)
	v_add_f32_e32 v66, v64, v65
	v_lshl_add_u64 v[64:65], v[104:105], 2, s[10:11]
	global_atomic_add_f32 v[64:65], v66, off
; __device__ __forceinline__ unsigned cvt_pk_bf16(float lo, float hi) { unsigned r; asm volatile("v_cvt_pk_bf16_f32 %0, %1, %2" : "=v"(r) : "v"(lo), "v"(hi)); return r; }
;     __device__ __forceinline__ void row_out(const f32x4 v0, const f32x4 v1, int row, int col, float& ss) const {
;         if (C) { float* rowp = C + (size_t)row * ldc + col; __builtin_nontemporal_store(v0, (f32x4*)rowp); __builtin_nontemporal_store(v1, (f32x4*)(rowp + 4)); }
;         if (wxb) { u32x4 w; w.x = cvt_pk_bf16(v0[0], v0[1]); w.y = cvt_pk_bf16(v0[2], v0[3]); w.z = cvt_pk_bf16(v1[0], v1[1]); w.w = cvt_pk_bf16(v1[2], v1[3]);
;             *(u32x4*)(XB0 + (size_t)row * ldc + col) = w;
;             ss += (v0[0] * v0[0] + v0[1] * v0[1]) + (v0[2] * v0[2] + v0[3] * v0[3]) + (v1[0] * v1[0] + v1[1] * v1[1]) + (v1[2] * v1[2] + v1[3] * v1[3]); }
;     __device__ __forceinline__ void operator()(const f32x4 (&acc)[2][2][4][2], const Unit& u, int wr, int wc, int fr, int fq) const {
;     ...
;               for (int mh = 0; mh < 4; mh += 2) {
;                 u32x4 rw[2][2];
; #pragma unroll
;                 for (int mm = 0; mm < 2; ++mm) { const int row = row0 + ai * HALF + (mh + mm) * 16;
; #pragma unroll
;                     for (int bj = 0; bj < 2; ++bj) if (bj == 0 || !u.q) rw[mm][bj] = *(const u32x4*)(XB0 + (size_t)row * ldc + col0 + bj * HALF); }
; #pragma unroll
;                 for (int mm = 0; mm < 2; ++mm) { const int m = mh + mm, row = row0 + ai * HALF + m * 16; float ss = 0.f;
; #pragma unroll
;                     for (int bj = 0; bj < 2; ++bj) if (bj == 0 || !u.q) { const u32x4 w = rw[mm][bj];
;                         const f32x4 v0 = acc[ai][bj][m][0] + (f32x4){bf_lo(w.x), bf_hi(w.x), bf_lo(w.y), bf_hi(w.y)}, v1 = acc[ai][bj][m][1] + (f32x4){bf_lo(w.z), bf_hi(w.z), bf_lo(w.w), bf_hi(w.w)};
;                         row_out(v0, v1, row, col0 + bj * HALF, ss); }
;                     if (wxb) { ss += __shfl_xor(ss, 16); ss += __shfl_xor(ss, 32); if (fq == 0) unsafeAtomicAdd(SS + row, ss); } }
.LBB0_2847:
	s_or_b64 exec, exec, s[6:7]
	v_add_u32_e32 v76, 0x80, v154
	v_ashrrev_i32_e32 v77, 31, v76
	v_lshlrev_b64 v[86:87], 11, v[76:77]
	s_waitcnt lgkmcnt(0)
	v_lshl_add_u64 v[64:65], v[156:157], 0, v[86:87]
	global_load_dwordx4 v[78:81], v[64:65], off
	global_load_dwordx4 v[82:85], v[64:65], off offset:256
	v_add_u32_e32 v72, 0x90, v154
	v_ashrrev_i32_e32 v73, 31, v72
	v_lshlrev_b64 v[74:75], 11, v[72:73]
	v_lshl_add_u64 v[64:65], v[156:157], 0, v[74:75]
	global_load_dwordx4 v[68:71], v[64:65], off
	s_nop 0
	global_load_dwordx4 v[64:67], v[64:65], off offset:256
	s_waitcnt vmcnt(3)
	v_lshlrev_b32_e32 v88, 16, v78
	v_and_b32_e32 v89, 0xffff0000, v78
	v_lshlrev_b32_e32 v78, 16, v79
	v_and_b32_e32 v79, 0xffff0000, v79
	s_waitcnt vmcnt(2)
	v_lshlrev_b32_e32 v92, 16, v82
	v_and_b32_e32 v93, 0xffff0000, v82
	v_lshlrev_b32_e32 v82, 16, v83
	v_and_b32_e32 v83, 0xffff0000, v83
	v_lshlrev_b32_e32 v90, 16, v80
	v_and_b32_e32 v91, 0xffff0000, v80
	v_lshlrev_b32_e32 v80, 16, v81
	v_and_b32_e32 v81, 0xffff0000, v81
	v_lshlrev_b32_e32 v94, 16, v84
	v_and_b32_e32 v95, 0xffff0000, v84
	v_lshlrev_b32_e32 v84, 16, v85
	v_and_b32_e32 v85, 0xffff0000, v85
	v_pk_add_f32 v[62:63], v[62:63], v[78:79]
	v_pk_add_f32 v[60:61], v[60:61], v[88:89]
	v_pk_add_f32 v[54:55], v[54:55], v[82:83]
	v_pk_add_f32 v[52:53], v[52:53], v[92:93]
	v_pk_add_f32 v[58:59], v[58:59], v[80:81]
	v_pk_add_f32 v[56:57], v[56:57], v[90:91]
	v_pk_add_f32 v[78:79], v[50:51], v[84:85]
	v_pk_add_f32 v[80:81], v[48:49], v[94:95]
	v_cvt_pk_bf16_f32 v48, v60, v61
	v_cvt_pk_bf16_f32 v49, v62, v63
	v_mul_f32_e32 v61, v61, v61
	v_mul_f32_e32 v63, v63, v63
	v_mul_f32_e32 v84, v53, v53
	v_mul_f32_e32 v85, v55, v55
	v_cvt_pk_bf16_f32 v50, v56, v57
	v_cvt_pk_bf16_f32 v51, v58, v59
	v_mul_f32_e32 v57, v57, v57
	v_mul_f32_e32 v59, v59, v59
	v_mul_f32_e32 v83, v81, v81
	v_fmac_f32_e32 v61, v60, v60
	v_fmac_f32_e32 v63, v62, v62
	v_fmac_f32_e32 v84, v52, v52
	v_fmac_f32_e32 v85, v54, v54
	v_mul_f32_e32 v82, v79, v79
	v_fmac_f32_e32 v57, v56, v56
	v_fmac_f32_e32 v59, v58, v58
	v_fmac_f32_e32 v83, v80, v80
	v_add_f32_e32 v56, v61, v63
	v_add_f32_e32 v58, v84, v85
	v_fmac_f32_e32 v82, v78, v78
	v_add_f32_e32 v56, v57, v56
	v_add_f32_e32 v57, v83, v58
	v_add_f32_e32 v56, v59, v56
	v_add_f32_e32 v57, v82, v57
	v_add_f32_e32 v58, v56, v57
	ds_bpermute_b32 v59, v169, v58
	v_lshl_add_u64 v[56:57], s[96:97], 0, v[86:87]
	v_lshl_add_u64 v[56:57], v[152:153], 1, v[56:57]
	global_store_dwordx4 v[56:57], v[48:51], off sc1
	s_waitcnt lgkmcnt(0)
	s_nop 0
	v_add_f32_e32 v48, v58, v59
	ds_bpermute_b32 v49, v112, v48
	v_cvt_pk_bf16_f32 v50, v52, v53
	v_cvt_pk_bf16_f32 v51, v54, v55
	v_cvt_pk_bf16_f32 v52, v80, v81
	v_cvt_pk_bf16_f32 v53, v78, v79
	global_store_dwordx4 v[56:57], v[50:53], off offset:256 sc1
	s_and_saveexec_b64 s[6:7], vcc
	s_cbranch_execz .LBB0_2849
	s_waitcnt lgkmcnt(0)
	v_add_f32_e32 v50, v48, v49
	v_lshl_add_u64 v[48:49], v[76:77], 2, s[10:11]
	global_atomic_add_f32 v[48:49], v50, off
.LBB0_2849:
	s_or_b64 exec, exec, s[6:7]
	s_waitcnt vmcnt(3)
	v_lshlrev_b32_e32 v48, 16, v68
	s_waitcnt lgkmcnt(0)
	v_and_b32_e32 v49, 0xffff0000, v68
	v_lshlrev_b32_e32 v50, 16, v69
	v_and_b32_e32 v51, 0xffff0000, v69
	v_pk_add_f32 v[44:45], v[44:45], v[48:49]
	v_lshlrev_b32_e32 v48, 16, v70
	v_and_b32_e32 v49, 0xffff0000, v70
	v_pk_add_f32 v[46:47], v[46:47], v[50:51]
	v_pk_add_f32 v[48:49], v[40:41], v[48:49]
	v_cvt_pk_bf16_f32 v40, v44, v45
	v_mul_f32_e32 v45, v45, v45
	v_fmac_f32_e32 v45, v44, v44
	v_mul_f32_e32 v44, v47, v47
	v_fmac_f32_e32 v44, v46, v46
	v_lshlrev_b32_e32 v50, 16, v71
	v_and_b32_e32 v51, 0xffff0000, v71
	v_add_f32_e32 v44, v45, v44
	v_mul_f32_e32 v45, v49, v49
	v_pk_add_f32 v[50:51], v[42:43], v[50:51]
	v_fmac_f32_e32 v45, v48, v48
	v_add_f32_e32 v44, v45, v44
	v_mul_f32_e32 v45, v51, v51
	v_fmac_f32_e32 v45, v50, v50
	v_cvt_pk_bf16_f32 v41, v46, v47
	v_cvt_pk_bf16_f32 v42, v48, v49
	v_add_f32_e32 v48, v45, v44
	s_waitcnt vmcnt(2)
	v_lshlrev_b32_e32 v44, 16, v64
	v_and_b32_e32 v45, 0xffff0000, v64
	v_lshlrev_b32_e32 v46, 16, v65
	v_and_b32_e32 v47, 0xffff0000, v65
	v_pk_add_f32 v[38:39], v[38:39], v[46:47]
	v_pk_add_f32 v[36:37], v[36:37], v[44:45]
	v_lshlrev_b32_e32 v44, 16, v66
	v_and_b32_e32 v45, 0xffff0000, v66
	v_lshlrev_b32_e32 v46, 16, v67
	v_and_b32_e32 v47, 0xffff0000, v67
	v_pk_add_f32 v[46:47], v[34:35], v[46:47]
	v_pk_add_f32 v[44:45], v[32:33], v[44:45]
	v_mul_f32_e32 v34, v37, v37
	v_mul_f32_e32 v35, v39, v39
	v_mul_f32_e32 v33, v45, v45
	v_fmac_f32_e32 v34, v36, v36
	v_fmac_f32_e32 v35, v38, v38
	v_mul_f32_e32 v32, v47, v47
	v_fmac_f32_e32 v33, v44, v44
	v_add_f32_e32 v34, v34, v35
	v_fmac_f32_e32 v32, v46, v46
	v_add_f32_e32 v33, v33, v34
	v_add_f32_e32 v32, v32, v33
	v_add_f32_e32 v35, v48, v32
	v_cvt_pk_bf16_f32 v43, v50, v51
	ds_bpermute_b32 v50, v169, v35
	v_lshl_add_u64 v[32:33], s[96:97], 0, v[74:75]
	v_lshl_add_u64 v[48:49], v[152:153], 1, v[32:33]
	global_store_dwordx4 v[48:49], v[40:43], off sc1
	v_cvt_pk_bf16_f32 v34, v36, v37
	s_waitcnt lgkmcnt(0)
	v_add_f32_e32 v32, v35, v50
	ds_bpermute_b32 v33, v112, v32
	v_cvt_pk_bf16_f32 v35, v38, v39
	v_cvt_pk_bf16_f32 v36, v44, v45
	v_cvt_pk_bf16_f32 v37, v46, v47
	global_store_dwordx4 v[48:49], v[34:37], off offset:256 sc1
	s_and_saveexec_b64 s[6:7], vcc
	s_cbranch_execz .LBB0_2851
	s_waitcnt lgkmcnt(0)
	v_add_f32_e32 v34, v32, v33
	v_lshl_add_u64 v[32:33], v[72:73], 2, s[10:11]
	global_atomic_add_f32 v[32:33], v34, off
; __device__ __forceinline__ unsigned cvt_pk_bf16(float lo, float hi) { unsigned r; asm volatile("v_cvt_pk_bf16_f32 %0, %1, %2" : "=v"(r) : "v"(lo), "v"(hi)); return r; }
;     __device__ __forceinline__ void row_out(const f32x4 v0, const f32x4 v1, int row, int col, float& ss) const {
;         if (C) { float* rowp = C + (size_t)row * ldc + col; __builtin_nontemporal_store(v0, (f32x4*)rowp); __builtin_nontemporal_store(v1, (f32x4*)(rowp + 4)); }
;         if (wxb) { u32x4 w; w.x = cvt_pk_bf16(v0[0], v0[1]); w.y = cvt_pk_bf16(v0[2], v0[3]); w.z = cvt_pk_bf16(v1[0], v1[1]); w.w = cvt_pk_bf16(v1[2], v1[3]);
;             *(u32x4*)(XB0 + (size_t)row * ldc + col) = w;
;             ss += (v0[0] * v0[0] + v0[1] * v0[1]) + (v0[2] * v0[2] + v0[3] * v0[3]) + (v1[0] * v1[0] + v1[1] * v1[1]) + (v1[2] * v1[2] + v1[3] * v1[3]); }
;     __device__ __forceinline__ void operator()(const f32x4 (&acc)[2][2][4][2], const Unit& u, int wr, int wc, int fr, int fq) const {
;     ...
;               for (int mh = 0; mh < 4; mh += 2) {
;                 u32x4 rw[2][2];
; #pragma unroll
;                 for (int mm = 0; mm < 2; ++mm) { const int row = row0 + ai * HALF + (mh + mm) * 16;
; #pragma unroll
;                     for (int bj = 0; bj < 2; ++bj) if (bj == 0 || !u.q) rw[mm][bj] = *(const u32x4*)(XB0 + (size_t)row * ldc + col0 + bj * HALF); }
; #pragma unroll
;                 for (int mm = 0; mm < 2; ++mm) { const int m = mh + mm, row = row0 + ai * HALF + m * 16; float ss = 0.f;
; #pragma unroll
;                     for (int bj = 0; bj < 2; ++bj) if (bj == 0 || !u.q) { const u32x4 w = rw[mm][bj];
;                         const f32x4 v0 = acc[ai][bj][m][0] + (f32x4){bf_lo(w.x), bf_hi(w.x), bf_lo(w.y), bf_hi(w.y)}, v1 = acc[ai][bj][m][1] + (f32x4){bf_lo(w.z), bf_hi(w.z), bf_lo(w.w), bf_hi(w.w)};
;                         row_out(v0, v1, row, col0 + bj * HALF, ss); }
;                     if (wxb) { ss += __shfl_xor(ss, 16); ss += __shfl_xor(ss, 32); if (fq == 0) unsafeAtomicAdd(SS + row, ss); } }
.LBB0_2851:
	s_or_b64 exec, exec, s[6:7]
	v_add_u32_e32 v44, 0xa0, v154
	v_ashrrev_i32_e32 v45, 31, v44
	v_lshlrev_b64 v[54:55], 11, v[44:45]
	s_waitcnt lgkmcnt(0)
	v_lshl_add_u64 v[32:33], v[156:157], 0, v[54:55]
	global_load_dwordx4 v[46:49], v[32:33], off
	global_load_dwordx4 v[50:53], v[32:33], off offset:256
	v_add_u32_e32 v40, 0xb0, v154
	v_ashrrev_i32_e32 v41, 31, v40
	v_lshlrev_b64 v[42:43], 11, v[40:41]
	v_lshl_add_u64 v[32:33], v[156:157], 0, v[42:43]
	global_load_dwordx4 v[36:39], v[32:33], off
	s_nop 0
	global_load_dwordx4 v[32:35], v[32:33], off offset:256
	s_waitcnt vmcnt(3)
	v_lshlrev_b32_e32 v56, 16, v46
	v_and_b32_e32 v57, 0xffff0000, v46
	v_lshlrev_b32_e32 v46, 16, v47
	v_and_b32_e32 v47, 0xffff0000, v47
	s_waitcnt vmcnt(2)
	v_lshlrev_b32_e32 v60, 16, v50
	v_and_b32_e32 v61, 0xffff0000, v50
	v_lshlrev_b32_e32 v50, 16, v51
	v_and_b32_e32 v51, 0xffff0000, v51
	v_lshlrev_b32_e32 v58, 16, v48
	v_and_b32_e32 v59, 0xffff0000, v48
	v_lshlrev_b32_e32 v48, 16, v49
	v_and_b32_e32 v49, 0xffff0000, v49
	v_lshlrev_b32_e32 v62, 16, v52
	v_and_b32_e32 v63, 0xffff0000, v52
	v_lshlrev_b32_e32 v52, 16, v53
	v_and_b32_e32 v53, 0xffff0000, v53
	v_pk_add_f32 v[30:31], v[30:31], v[46:47]
	v_pk_add_f32 v[28:29], v[28:29], v[56:57]
	v_pk_add_f32 v[22:23], v[22:23], v[50:51]
	v_pk_add_f32 v[20:21], v[20:21], v[60:61]
	v_pk_add_f32 v[26:27], v[26:27], v[48:49]
	v_pk_add_f32 v[24:25], v[24:25], v[58:59]
	v_pk_add_f32 v[46:47], v[18:19], v[52:53]
	v_pk_add_f32 v[48:49], v[16:17], v[62:63]
	v_cvt_pk_bf16_f32 v16, v28, v29
	v_cvt_pk_bf16_f32 v17, v30, v31
	v_mul_f32_e32 v29, v29, v29
	v_mul_f32_e32 v31, v31, v31
	v_mul_f32_e32 v52, v21, v21
	v_mul_f32_e32 v53, v23, v23
	v_cvt_pk_bf16_f32 v18, v24, v25
	v_cvt_pk_bf16_f32 v19, v26, v27
	v_mul_f32_e32 v25, v25, v25
	v_mul_f32_e32 v27, v27, v27
	v_mul_f32_e32 v51, v49, v49
	v_fmac_f32_e32 v29, v28, v28
	v_fmac_f32_e32 v31, v30, v30
	v_fmac_f32_e32 v52, v20, v20
	v_fmac_f32_e32 v53, v22, v22
	v_mul_f32_e32 v50, v47, v47
	v_fmac_f32_e32 v25, v24, v24
	v_fmac_f32_e32 v27, v26, v26
	v_fmac_f32_e32 v51, v48, v48
	v_add_f32_e32 v24, v29, v31
	v_add_f32_e32 v26, v52, v53
	v_fmac_f32_e32 v50, v46, v46
	v_add_f32_e32 v24, v25, v24
	v_add_f32_e32 v25, v51, v26
	v_add_f32_e32 v24, v27, v24
	v_add_f32_e32 v25, v50, v25
	v_add_f32_e32 v26, v24, v25
	ds_bpermute_b32 v27, v169, v26
	v_lshl_add_u64 v[24:25], s[96:97], 0, v[54:55]
	v_lshl_add_u64 v[24:25], v[152:153], 1, v[24:25]
	global_store_dwordx4 v[24:25], v[16:19], off sc1
	s_waitcnt lgkmcnt(0)
	s_nop 0
	v_add_f32_e32 v16, v26, v27
	ds_bpermute_b32 v17, v112, v16
	v_cvt_pk_bf16_f32 v18, v20, v21
	v_cvt_pk_bf16_f32 v19, v22, v23
	v_cvt_pk_bf16_f32 v20, v48, v49
	v_cvt_pk_bf16_f32 v21, v46, v47
	global_store_dwordx4 v[24:25], v[18:21], off offset:256 sc1
	s_and_saveexec_b64 s[6:7], vcc
	s_cbranch_execz .LBB0_2853
	s_waitcnt lgkmcnt(0)
	v_add_f32_e32 v18, v16, v17
	v_lshl_add_u64 v[16:17], v[44:45], 2, s[10:11]
	global_atomic_add_f32 v[16:17], v18, off
.LBB0_2853:
	s_or_b64 exec, exec, s[6:7]
	s_waitcnt vmcnt(3)
	v_lshlrev_b32_e32 v16, 16, v36
	s_waitcnt lgkmcnt(0)
	v_and_b32_e32 v17, 0xffff0000, v36
	v_lshlrev_b32_e32 v18, 16, v37
	v_and_b32_e32 v19, 0xffff0000, v37
	v_pk_add_f32 v[12:13], v[12:13], v[16:17]
	v_lshlrev_b32_e32 v16, 16, v38
	v_and_b32_e32 v17, 0xffff0000, v38
	v_pk_add_f32 v[14:15], v[14:15], v[18:19]
	v_pk_add_f32 v[16:17], v[8:9], v[16:17]
	v_cvt_pk_bf16_f32 v8, v12, v13
	v_mul_f32_e32 v13, v13, v13
	v_fmac_f32_e32 v13, v12, v12
	v_mul_f32_e32 v12, v15, v15
	v_fmac_f32_e32 v12, v14, v14
	v_lshlrev_b32_e32 v18, 16, v39
	v_and_b32_e32 v19, 0xffff0000, v39
	v_add_f32_e32 v12, v13, v12
	v_mul_f32_e32 v13, v17, v17
	v_pk_add_f32 v[18:19], v[10:11], v[18:19]
	v_fmac_f32_e32 v13, v16, v16
	v_add_f32_e32 v12, v13, v12
	v_mul_f32_e32 v13, v19, v19
	v_fmac_f32_e32 v13, v18, v18
	v_cvt_pk_bf16_f32 v9, v14, v15
	v_cvt_pk_bf16_f32 v10, v16, v17
	v_add_f32_e32 v16, v13, v12
	s_waitcnt vmcnt(2)
	v_lshlrev_b32_e32 v12, 16, v32
	v_and_b32_e32 v13, 0xffff0000, v32
	v_lshlrev_b32_e32 v14, 16, v33
	v_and_b32_e32 v15, 0xffff0000, v33
	v_pk_add_f32 v[6:7], v[6:7], v[14:15]
	v_pk_add_f32 v[4:5], v[4:5], v[12:13]
	v_lshlrev_b32_e32 v12, 16, v34
	v_and_b32_e32 v13, 0xffff0000, v34
	v_lshlrev_b32_e32 v14, 16, v35
	v_and_b32_e32 v15, 0xffff0000, v35
	v_pk_add_f32 v[14:15], v[2:3], v[14:15]
	v_pk_add_f32 v[12:13], v[0:1], v[12:13]
	v_mul_f32_e32 v2, v5, v5
	v_mul_f32_e32 v3, v7, v7
	v_mul_f32_e32 v1, v13, v13
	v_fmac_f32_e32 v2, v4, v4
	v_fmac_f32_e32 v3, v6, v6
	v_mul_f32_e32 v0, v15, v15
	v_fmac_f32_e32 v1, v12, v12
	v_add_f32_e32 v2, v2, v3
	v_fmac_f32_e32 v0, v14, v14
	v_add_f32_e32 v1, v1, v2
	v_add_f32_e32 v0, v0, v1
	v_add_f32_e32 v3, v16, v0
	v_cvt_pk_bf16_f32 v11, v18, v19
	ds_bpermute_b32 v18, v169, v3
	v_lshl_add_u64 v[0:1], s[96:97], 0, v[42:43]
	v_lshl_add_u64 v[16:17], v[152:153], 1, v[0:1]
	global_store_dwordx4 v[16:17], v[8:11], off sc1
	v_cvt_pk_bf16_f32 v2, v4, v5
	s_waitcnt lgkmcnt(0)
	v_add_f32_e32 v0, v3, v18
	ds_bpermute_b32 v1, v112, v0
	v_cvt_pk_bf16_f32 v3, v6, v7
	v_cvt_pk_bf16_f32 v4, v12, v13
	v_cvt_pk_bf16_f32 v5, v14, v15
	global_store_dwordx4 v[16:17], v[2:5], off offset:256 sc1
	s_and_saveexec_b64 s[6:7], vcc
	s_cbranch_execz .LBB0_2855
	v_lshl_add_u64 v[2:3], v[40:41], 2, s[10:11]
	s_waitcnt lgkmcnt(0)
	v_add_f32_e32 v0, v0, v1
	global_atomic_add_f32 v[2:3], v0, off

; __device__ __forceinline__ unsigned cvt_pk_bf16(float lo, float hi) { unsigned r; asm volatile("v_cvt_pk_bf16_f32 %0, %1, %2" : "=v"(r) : "v"(lo), "v"(hi)); return r; }
;     __device__ __forceinline__ void operator()(const f32x4 (&acc)[2][2][4][2], const Unit& u, int wr, int wc, int fr, int fq) const {
;     ...
;             for (int m = 0; m < 4; ++m) { const int row = row0 + ai * HALF + m * 16; bf16_t* rowp = G + (size_t)row * 2816 + col0;
;                 float* co = nullptr;
;                 if (row < 32768) { const int t = row & 8191; if (t >= 8190) co = outP + ((size_t)(row >> 13) * 2 + (t - 8190)) * 2816 + col0; }
;                 else { const int i = row & 7; if (i >= 6) co = outS + ((size_t)((row - 32768) >> 3) * 2 + (i - 6)) * 2816 + col0; }
;                 const float rs = rsqrtf(rsv[ai][m] * (1.f / 1024.f) + 1e-6f);
; #pragma unroll
;                 for (int bj = 0; bj < 2; ++bj) { const f32x4 v0 = acc[ai][bj][m][0] * rs, v1 = acc[ai][bj][m][1] * rs;
;                     u32x4 w; w.x = cvt_pk_bf16(v0[0], v0[1]); w.y = cvt_pk_bf16(v0[2], v0[3]); w.z = cvt_pk_bf16(v1[0], v1[1]); w.w = cvt_pk_bf16(v1[2], v1[3]);
;                     *(u32x4*)(rowp + bj * HALF) = w;
;                     if (co) { *(f32x4*)(co + bj * HALF) = v0; *(f32x4*)(co + bj * HALF + 4) = v1; } } }
.LBB0_2967:
	s_or_b64 exec, exec, s[26:27]
	s_waitcnt vmcnt(0)
	v_fmamk_f32 v142, v142, 0x3a800000, v223
	v_mul_f32_e32 v143, 0x4b800000, v142
	v_cmp_gt_f32_e32 vcc, s53, v142
	v_readlane_b32 s26, v240, 12
	v_readlane_b32 s27, v240, 13
	v_cndmask_b32_e32 v142, v142, v143, vcc
	v_rsq_f32_e32 v149, v142
	v_mov_b64_e32 v[144:145], s[26:27]
	v_mad_i64_i32 v[142:143], s[26:27], v2, s52, v[144:145]
	v_mul_f32_e32 v144, 0x45800000, v149
	v_cndmask_b32_e32 v144, v149, v144, vcc
	v_lshl_add_u64 v[142:143], v[132:133], 1, v[142:143]
	v_cmp_ne_u64_e32 vcc, 0, v[140:141]
	v_pk_mul_f32 v[130:131], v[130:131], v[144:145] op_sel_hi:[1,0]
	v_pk_mul_f32 v[128:129], v[128:129], v[144:145] op_sel_hi:[1,0]
	v_pk_mul_f32 v[126:127], v[126:127], v[144:145] op_sel_hi:[1,0]
	v_pk_mul_f32 v[124:125], v[124:125], v[144:145] op_sel_hi:[1,0]
	v_cvt_pk_bf16_f32 v150, v128, v129
	v_cvt_pk_bf16_f32 v151, v130, v131
	s_nop 0
	v_cvt_pk_bf16_f32 v152, v124, v125
	v_cvt_pk_bf16_f32 v153, v126, v127
	global_store_dwordx4 v[142:143], v[150:153], off sc1
	s_and_saveexec_b64 s[26:27], vcc
	s_cbranch_execz .LBB0_2969
	global_store_dwordx4 v[140:141], v[128:131], off sc1
	global_store_dwordx4 v[140:141], v[124:127], off offset:16 sc1
.LBB0_2969:
	s_or_b64 exec, exec, s[26:27]
	v_mov_b32_e32 v145, v144
	v_mov_b32_e32 v124, v144
	v_mov_b32_e32 v125, v144
	v_pk_mul_f32 v[122:123], v[122:123], v[124:125]
	v_pk_mul_f32 v[120:121], v[120:121], v[144:145]
	v_pk_mul_f32 v[118:119], v[118:119], v[124:125]
	v_pk_mul_f32 v[116:117], v[116:117], v[144:145]
	v_cvt_pk_bf16_f32 v124, v120, v121
	v_cvt_pk_bf16_f32 v125, v122, v123
	s_nop 0
	v_cvt_pk_bf16_f32 v126, v116, v117
	v_cvt_pk_bf16_f32 v127, v118, v119
	global_store_dwordx4 v[142:143], v[124:127], off offset:256 sc1
	s_and_saveexec_b64 s[26:27], vcc
	s_cbranch_execz .LBB0_2971
	global_store_dwordx4 v[140:141], v[120:123], off offset:512 sc1
	global_store_dwordx4 v[140:141], v[116:119], off offset:528 sc1

; __device__ __forceinline__ unsigned cvt_pk_bf16(float lo, float hi) { unsigned r; asm volatile("v_cvt_pk_bf16_f32 %0, %1, %2" : "=v"(r) : "v"(lo), "v"(hi)); return r; }
;     __device__ __forceinline__ void operator()(const f32x4 (&acc)[2][2][4][2], const Unit& u, int wr, int wc, int fr, int fq) const {
;     ...
;             for (int m = 0; m < 4; ++m) { const int row = row0 + ai * HALF + m * 16; bf16_t* rowp = G + (size_t)row * 2816 + col0;
;                 float* co = nullptr;
;                 if (row < 32768) { const int t = row & 8191; if (t >= 8190) co = outP + ((size_t)(row >> 13) * 2 + (t - 8190)) * 2816 + col0; }
;                 else { const int i = row & 7; if (i >= 6) co = outS + ((size_t)((row - 32768) >> 3) * 2 + (i - 6)) * 2816 + col0; }
;                 const float rs = rsqrtf(rsv[ai][m] * (1.f / 1024.f) + 1e-6f);
; #pragma unroll
;                 for (int bj = 0; bj < 2; ++bj) { const f32x4 v0 = acc[ai][bj][m][0] * rs, v1 = acc[ai][bj][m][1] * rs;
;                     u32x4 w; w.x = cvt_pk_bf16(v0[0], v0[1]); w.y = cvt_pk_bf16(v0[2], v0[3]); w.z = cvt_pk_bf16(v1[0], v1[1]); w.w = cvt_pk_bf16(v1[2], v1[3]);
;                     *(u32x4*)(rowp + bj * HALF) = w;
;                     if (co) { *(f32x4*)(co + bj * HALF) = v0; *(f32x4*)(co + bj * HALF + 4) = v1; } } }
.LBB0_2979:
	s_or_b64 exec, exec, s[26:27]
	v_fmamk_f32 v120, v148, 0x3a800000, v223
	v_mul_f32_e32 v121, 0x4b800000, v120
	v_cmp_gt_f32_e32 vcc, s53, v120
	v_readlane_b32 s26, v240, 12
	v_readlane_b32 s27, v240, 13
	v_cndmask_b32_e32 v120, v120, v121, vcc
	v_rsq_f32_e32 v120, v120
	v_mov_b64_e32 v[118:119], s[26:27]
	v_mad_i64_i32 v[118:119], s[26:27], v138, s52, v[118:119]
	v_mul_f32_e32 v121, 0x45800000, v120
	v_cndmask_b32_e32 v120, v120, v121, vcc
	v_lshl_add_u64 v[118:119], v[132:133], 1, v[118:119]
	v_cmp_ne_u64_e32 vcc, 0, v[116:117]
	v_pk_mul_f32 v[114:115], v[114:115], v[120:121] op_sel_hi:[1,0]
	v_pk_mul_f32 v[112:113], v[112:113], v[120:121] op_sel_hi:[1,0]
	v_pk_mul_f32 v[110:111], v[110:111], v[120:121] op_sel_hi:[1,0]
	v_pk_mul_f32 v[108:109], v[108:109], v[120:121] op_sel_hi:[1,0]
	v_cvt_pk_bf16_f32 v122, v112, v113
	v_cvt_pk_bf16_f32 v123, v114, v115
	s_nop 0
	v_cvt_pk_bf16_f32 v124, v108, v109
	v_cvt_pk_bf16_f32 v125, v110, v111
	global_store_dwordx4 v[118:119], v[122:125], off sc1
	s_and_saveexec_b64 s[26:27], vcc
	s_cbranch_execz .LBB0_2981
	global_store_dwordx4 v[116:117], v[112:115], off sc1
	global_store_dwordx4 v[116:117], v[108:111], off offset:16 sc1
.LBB0_2981:
	s_or_b64 exec, exec, s[26:27]
	v_mov_b32_e32 v121, v120
	v_mov_b32_e32 v108, v120
	v_mov_b32_e32 v109, v120
	v_pk_mul_f32 v[106:107], v[106:107], v[108:109]
	v_pk_mul_f32 v[104:105], v[104:105], v[120:121]
	v_pk_mul_f32 v[102:103], v[102:103], v[108:109]
	v_pk_mul_f32 v[100:101], v[100:101], v[120:121]
	v_cvt_pk_bf16_f32 v108, v104, v105
	v_cvt_pk_bf16_f32 v109, v106, v107
	s_nop 0
	v_cvt_pk_bf16_f32 v110, v100, v101
	v_cvt_pk_bf16_f32 v111, v102, v103
	global_store_dwordx4 v[118:119], v[108:111], off offset:256 sc1
	s_and_saveexec_b64 s[26:27], vcc
	s_cbranch_execz .LBB0_2983
	global_store_dwordx4 v[116:117], v[104:107], off offset:512 sc1
	global_store_dwordx4 v[116:117], v[100:103], off offset:528 sc1

; __device__ __forceinline__ unsigned cvt_pk_bf16(float lo, float hi) { unsigned r; asm volatile("v_cvt_pk_bf16_f32 %0, %1, %2" : "=v"(r) : "v"(lo), "v"(hi)); return r; }
;     __device__ __forceinline__ void operator()(const f32x4 (&acc)[2][2][4][2], const Unit& u, int wr, int wc, int fr, int fq) const {
;     ...
;             for (int m = 0; m < 4; ++m) { const int row = row0 + ai * HALF + m * 16; bf16_t* rowp = G + (size_t)row * 2816 + col0;
;                 float* co = nullptr;
;                 if (row < 32768) { const int t = row & 8191; if (t >= 8190) co = outP + ((size_t)(row >> 13) * 2 + (t - 8190)) * 2816 + col0; }
;                 else { const int i = row & 7; if (i >= 6) co = outS + ((size_t)((row - 32768) >> 3) * 2 + (i - 6)) * 2816 + col0; }
;                 const float rs = rsqrtf(rsv[ai][m] * (1.f / 1024.f) + 1e-6f);
; #pragma unroll
;                 for (int bj = 0; bj < 2; ++bj) { const f32x4 v0 = acc[ai][bj][m][0] * rs, v1 = acc[ai][bj][m][1] * rs;
;                     u32x4 w; w.x = cvt_pk_bf16(v0[0], v0[1]); w.y = cvt_pk_bf16(v0[2], v0[3]); w.z = cvt_pk_bf16(v1[0], v1[1]); w.w = cvt_pk_bf16(v1[2], v1[3]);
;                     *(u32x4*)(rowp + bj * HALF) = w;
;                     if (co) { *(f32x4*)(co + bj * HALF) = v0; *(f32x4*)(co + bj * HALF + 4) = v1; } } }
.LBB0_2991:
	s_or_b64 exec, exec, s[26:27]
	v_fmamk_f32 v104, v147, 0x3a800000, v223
	v_mul_f32_e32 v105, 0x4b800000, v104
	v_cmp_gt_f32_e32 vcc, s53, v104
	v_readlane_b32 s26, v240, 12
	v_readlane_b32 s27, v240, 13
	v_cndmask_b32_e32 v104, v104, v105, vcc
	v_rsq_f32_e32 v104, v104
	v_mov_b64_e32 v[102:103], s[26:27]
	v_mad_i64_i32 v[102:103], s[26:27], v136, s52, v[102:103]
	v_mul_f32_e32 v105, 0x45800000, v104
	v_cndmask_b32_e32 v104, v104, v105, vcc
	v_lshl_add_u64 v[102:103], v[132:133], 1, v[102:103]
	v_cmp_ne_u64_e32 vcc, 0, v[100:101]
	v_pk_mul_f32 v[98:99], v[98:99], v[104:105] op_sel_hi:[1,0]
	v_pk_mul_f32 v[96:97], v[96:97], v[104:105] op_sel_hi:[1,0]
	v_pk_mul_f32 v[94:95], v[94:95], v[104:105] op_sel_hi:[1,0]
	v_pk_mul_f32 v[92:93], v[92:93], v[104:105] op_sel_hi:[1,0]
	v_cvt_pk_bf16_f32 v106, v96, v97
	v_cvt_pk_bf16_f32 v107, v98, v99
	s_nop 0
	v_cvt_pk_bf16_f32 v108, v92, v93
	v_cvt_pk_bf16_f32 v109, v94, v95
	global_store_dwordx4 v[102:103], v[106:109], off sc1
	s_and_saveexec_b64 s[26:27], vcc
	s_cbranch_execz .LBB0_2993
	global_store_dwordx4 v[100:101], v[96:99], off sc1
	global_store_dwordx4 v[100:101], v[92:95], off offset:16 sc1
.LBB0_2993:
	s_or_b64 exec, exec, s[26:27]
	v_mov_b32_e32 v105, v104
	v_mov_b32_e32 v92, v104
	v_mov_b32_e32 v93, v104
	v_pk_mul_f32 v[90:91], v[90:91], v[92:93]
	v_pk_mul_f32 v[88:89], v[88:89], v[104:105]
	v_pk_mul_f32 v[86:87], v[86:87], v[92:93]
	v_pk_mul_f32 v[84:85], v[84:85], v[104:105]
	v_cvt_pk_bf16_f32 v92, v88, v89
	v_cvt_pk_bf16_f32 v93, v90, v91
	s_nop 0
	v_cvt_pk_bf16_f32 v94, v84, v85
	v_cvt_pk_bf16_f32 v95, v86, v87
	global_store_dwordx4 v[102:103], v[92:95], off offset:256 sc1
	s_and_saveexec_b64 s[26:27], vcc
	s_cbranch_execz .LBB0_2995
	global_store_dwordx4 v[100:101], v[88:91], off offset:512 sc1
	global_store_dwordx4 v[100:101], v[84:87], off offset:528 sc1

; __device__ __forceinline__ unsigned cvt_pk_bf16(float lo, float hi) { unsigned r; asm volatile("v_cvt_pk_bf16_f32 %0, %1, %2" : "=v"(r) : "v"(lo), "v"(hi)); return r; }
;     __device__ __forceinline__ void operator()(const f32x4 (&acc)[2][2][4][2], const Unit& u, int wr, int wc, int fr, int fq) const {
;     ...
;             for (int m = 0; m < 4; ++m) { const int row = row0 + ai * HALF + m * 16; bf16_t* rowp = G + (size_t)row * 2816 + col0;
;                 float* co = nullptr;
;                 if (row < 32768) { const int t = row & 8191; if (t >= 8190) co = outP + ((size_t)(row >> 13) * 2 + (t - 8190)) * 2816 + col0; }
;                 else { const int i = row & 7; if (i >= 6) co = outS + ((size_t)((row - 32768) >> 3) * 2 + (i - 6)) * 2816 + col0; }
;                 const float rs = rsqrtf(rsv[ai][m] * (1.f / 1024.f) + 1e-6f);
; #pragma unroll
;                 for (int bj = 0; bj < 2; ++bj) { const f32x4 v0 = acc[ai][bj][m][0] * rs, v1 = acc[ai][bj][m][1] * rs;
;                     u32x4 w; w.x = cvt_pk_bf16(v0[0], v0[1]); w.y = cvt_pk_bf16(v0[2], v0[3]); w.z = cvt_pk_bf16(v1[0], v1[1]); w.w = cvt_pk_bf16(v1[2], v1[3]);
;                     *(u32x4*)(rowp + bj * HALF) = w;
;                     if (co) { *(f32x4*)(co + bj * HALF) = v0; *(f32x4*)(co + bj * HALF + 4) = v1; } } }
.LBB0_3003:
	s_or_b64 exec, exec, s[26:27]
	v_fmamk_f32 v88, v146, 0x3a800000, v223
	v_mul_f32_e32 v89, 0x4b800000, v88
	v_cmp_gt_f32_e32 vcc, s53, v88
	v_readlane_b32 s26, v240, 12
	v_readlane_b32 s27, v240, 13
	v_cndmask_b32_e32 v88, v88, v89, vcc
	v_rsq_f32_e32 v88, v88
	v_mov_b64_e32 v[86:87], s[26:27]
	v_mad_i64_i32 v[86:87], s[26:27], v134, s52, v[86:87]
	v_mul_f32_e32 v89, 0x45800000, v88
	v_cndmask_b32_e32 v88, v88, v89, vcc
	v_lshl_add_u64 v[86:87], v[132:133], 1, v[86:87]
	v_cmp_ne_u64_e32 vcc, 0, v[84:85]
	v_pk_mul_f32 v[82:83], v[82:83], v[88:89] op_sel_hi:[1,0]
	v_pk_mul_f32 v[80:81], v[80:81], v[88:89] op_sel_hi:[1,0]
	v_pk_mul_f32 v[78:79], v[78:79], v[88:89] op_sel_hi:[1,0]
	v_pk_mul_f32 v[76:77], v[76:77], v[88:89] op_sel_hi:[1,0]
	v_cvt_pk_bf16_f32 v90, v80, v81
	v_cvt_pk_bf16_f32 v91, v82, v83
	s_nop 0
	v_cvt_pk_bf16_f32 v92, v76, v77
	v_cvt_pk_bf16_f32 v93, v78, v79
	global_store_dwordx4 v[86:87], v[90:93], off sc1
	s_and_saveexec_b64 s[26:27], vcc
	s_cbranch_execz .LBB0_3005
	global_store_dwordx4 v[84:85], v[80:83], off sc1
	global_store_dwordx4 v[84:85], v[76:79], off offset:16 sc1
.LBB0_3005:
	s_or_b64 exec, exec, s[26:27]
	v_mov_b32_e32 v89, v88
	v_mov_b32_e32 v76, v88
	v_mov_b32_e32 v77, v88
	v_pk_mul_f32 v[74:75], v[74:75], v[76:77]
	v_pk_mul_f32 v[72:73], v[72:73], v[88:89]
	v_pk_mul_f32 v[70:71], v[70:71], v[76:77]
	v_pk_mul_f32 v[68:69], v[68:69], v[88:89]
	v_cvt_pk_bf16_f32 v76, v72, v73
	v_cvt_pk_bf16_f32 v77, v74, v75
	s_nop 0
	v_cvt_pk_bf16_f32 v78, v68, v69
	v_cvt_pk_bf16_f32 v79, v70, v71
	global_store_dwordx4 v[86:87], v[76:79], off offset:256 sc1
	s_and_saveexec_b64 s[26:27], vcc
	s_cbranch_execz .LBB0_3056
	global_store_dwordx4 v[84:85], v[72:75], off offset:512 sc1
	global_store_dwordx4 v[84:85], v[68:71], off offset:528 sc1
	s_or_b64 exec, exec, s[26:27]
	s_and_b64 vcc, exec, s[6:7]
	s_cbranch_vccnz .LBB0_3057

; __device__ __forceinline__ unsigned cvt_pk_bf16(float lo, float hi) { unsigned r; asm volatile("v_cvt_pk_bf16_f32 %0, %1, %2" : "=v"(r) : "v"(lo), "v"(hi)); return r; }
;     __device__ __forceinline__ void operator()(const f32x4 (&acc)[2][2][4][2], const Unit& u, int wr, int wc, int fr, int fq) const {
;     ...
;             for (int m = 0; m < 4; ++m) { const int row = row0 + ai * HALF + m * 16; bf16_t* rowp = G + (size_t)row * 2816 + col0;
;                 float* co = nullptr;
;                 if (row < 32768) { const int t = row & 8191; if (t >= 8190) co = outP + ((size_t)(row >> 13) * 2 + (t - 8190)) * 2816 + col0; }
;                 else { const int i = row & 7; if (i >= 6) co = outS + ((size_t)((row - 32768) >> 3) * 2 + (i - 6)) * 2816 + col0; }
;                 const float rs = rsqrtf(rsv[ai][m] * (1.f / 1024.f) + 1e-6f);
; #pragma unroll
;                 for (int bj = 0; bj < 2; ++bj) { const f32x4 v0 = acc[ai][bj][m][0] * rs, v1 = acc[ai][bj][m][1] * rs;
;                     u32x4 w; w.x = cvt_pk_bf16(v0[0], v0[1]); w.y = cvt_pk_bf16(v0[2], v0[3]); w.z = cvt_pk_bf16(v1[0], v1[1]); w.w = cvt_pk_bf16(v1[2], v1[3]);
;                     *(u32x4*)(rowp + bj * HALF) = w;
;                     if (co) { *(f32x4*)(co + bj * HALF) = v0; *(f32x4*)(co + bj * HALF + 4) = v1; } } }
.LBB0_3015:
	s_or_b64 exec, exec, s[6:7]
	v_fmamk_f32 v71, v139, 0x3a800000, v223
	v_mul_f32_e32 v74, 0x4b800000, v71
	v_cmp_gt_f32_e32 vcc, s53, v71
	v_readlane_b32 s6, v240, 12
	v_readlane_b32 s7, v240, 13
	v_cndmask_b32_e32 v71, v71, v74, vcc
	v_rsq_f32_e32 v74, v71
	v_mov_b64_e32 v[72:73], s[6:7]
	v_mad_i64_i32 v[70:71], s[6:7], v70, s52, v[72:73]
	v_mul_f32_e32 v72, 0x45800000, v74
	v_cndmask_b32_e32 v72, v74, v72, vcc
	v_lshl_add_u64 v[70:71], v[132:133], 1, v[70:71]
	v_cmp_ne_u64_e32 vcc, 0, v[68:69]
	v_pk_mul_f32 v[66:67], v[66:67], v[72:73] op_sel_hi:[1,0]
	v_pk_mul_f32 v[64:65], v[64:65], v[72:73] op_sel_hi:[1,0]
	v_pk_mul_f32 v[62:63], v[62:63], v[72:73] op_sel_hi:[1,0]
	v_pk_mul_f32 v[60:61], v[60:61], v[72:73] op_sel_hi:[1,0]
	v_cvt_pk_bf16_f32 v74, v64, v65
	v_cvt_pk_bf16_f32 v75, v66, v67
	s_nop 0
	v_cvt_pk_bf16_f32 v76, v60, v61
	v_cvt_pk_bf16_f32 v77, v62, v63
	global_store_dwordx4 v[70:71], v[74:77], off sc1
	s_and_saveexec_b64 s[6:7], vcc
	s_cbranch_execz .LBB0_3017
	global_store_dwordx4 v[68:69], v[64:67], off sc1
	global_store_dwordx4 v[68:69], v[60:63], off offset:16 sc1
.LBB0_3017:
	s_or_b64 exec, exec, s[6:7]
	v_mov_b32_e32 v73, v72
	v_mov_b32_e32 v60, v72
	v_mov_b32_e32 v61, v72
	v_pk_mul_f32 v[58:59], v[58:59], v[60:61]
	v_pk_mul_f32 v[56:57], v[56:57], v[72:73]
	v_pk_mul_f32 v[54:55], v[54:55], v[60:61]
	v_pk_mul_f32 v[52:53], v[52:53], v[72:73]
	v_cvt_pk_bf16_f32 v60, v56, v57
	v_cvt_pk_bf16_f32 v61, v58, v59
	s_nop 0
	v_cvt_pk_bf16_f32 v62, v52, v53
	v_cvt_pk_bf16_f32 v63, v54, v55
	global_store_dwordx4 v[70:71], v[60:63], off offset:256 sc1
	s_and_saveexec_b64 s[6:7], vcc
	s_cbranch_execz .LBB0_3019
	global_store_dwordx4 v[68:69], v[56:59], off offset:512 sc1
	global_store_dwordx4 v[68:69], v[52:55], off offset:528 sc1

; __device__ __forceinline__ unsigned cvt_pk_bf16(float lo, float hi) { unsigned r; asm volatile("v_cvt_pk_bf16_f32 %0, %1, %2" : "=v"(r) : "v"(lo), "v"(hi)); return r; }
;     __device__ __forceinline__ void operator()(const f32x4 (&acc)[2][2][4][2], const Unit& u, int wr, int wc, int fr, int fq) const {
;     ...
;             for (int m = 0; m < 4; ++m) { const int row = row0 + ai * HALF + m * 16; bf16_t* rowp = G + (size_t)row * 2816 + col0;
;                 float* co = nullptr;
;                 if (row < 32768) { const int t = row & 8191; if (t >= 8190) co = outP + ((size_t)(row >> 13) * 2 + (t - 8190)) * 2816 + col0; }
;                 else { const int i = row & 7; if (i >= 6) co = outS + ((size_t)((row - 32768) >> 3) * 2 + (i - 6)) * 2816 + col0; }
;                 const float rs = rsqrtf(rsv[ai][m] * (1.f / 1024.f) + 1e-6f);
; #pragma unroll
;                 for (int bj = 0; bj < 2; ++bj) { const f32x4 v0 = acc[ai][bj][m][0] * rs, v1 = acc[ai][bj][m][1] * rs;
;                     u32x4 w; w.x = cvt_pk_bf16(v0[0], v0[1]); w.y = cvt_pk_bf16(v0[2], v0[3]); w.z = cvt_pk_bf16(v1[0], v1[1]); w.w = cvt_pk_bf16(v1[2], v1[3]);
;                     *(u32x4*)(rowp + bj * HALF) = w;
;                     if (co) { *(f32x4*)(co + bj * HALF) = v0; *(f32x4*)(co + bj * HALF + 4) = v1; } } }
.LBB0_3027:
	s_or_b64 exec, exec, s[6:7]
	v_fmamk_f32 v55, v137, 0x3a800000, v223
	v_mul_f32_e32 v58, 0x4b800000, v55
	v_cmp_gt_f32_e32 vcc, s53, v55
	v_readlane_b32 s6, v240, 12
	v_readlane_b32 s7, v240, 13
	v_cndmask_b32_e32 v55, v55, v58, vcc
	v_rsq_f32_e32 v58, v55
	v_mov_b64_e32 v[56:57], s[6:7]
	v_mad_i64_i32 v[54:55], s[6:7], v54, s52, v[56:57]
	v_mul_f32_e32 v56, 0x45800000, v58
	v_cndmask_b32_e32 v56, v58, v56, vcc
	v_lshl_add_u64 v[54:55], v[132:133], 1, v[54:55]
	v_cmp_ne_u64_e32 vcc, 0, v[52:53]
	v_pk_mul_f32 v[50:51], v[50:51], v[56:57] op_sel_hi:[1,0]
	v_pk_mul_f32 v[48:49], v[48:49], v[56:57] op_sel_hi:[1,0]
	v_pk_mul_f32 v[46:47], v[46:47], v[56:57] op_sel_hi:[1,0]
	v_pk_mul_f32 v[44:45], v[44:45], v[56:57] op_sel_hi:[1,0]
	v_cvt_pk_bf16_f32 v58, v48, v49
	v_cvt_pk_bf16_f32 v59, v50, v51
	s_nop 0
	v_cvt_pk_bf16_f32 v60, v44, v45
	v_cvt_pk_bf16_f32 v61, v46, v47
	global_store_dwordx4 v[54:55], v[58:61], off sc1
	s_and_saveexec_b64 s[6:7], vcc
	s_cbranch_execz .LBB0_3029
	global_store_dwordx4 v[52:53], v[48:51], off sc1
	global_store_dwordx4 v[52:53], v[44:47], off offset:16 sc1
.LBB0_3029:
	s_or_b64 exec, exec, s[6:7]
	v_mov_b32_e32 v57, v56
	v_mov_b32_e32 v44, v56
	v_mov_b32_e32 v45, v56
	v_pk_mul_f32 v[42:43], v[42:43], v[44:45]
	v_pk_mul_f32 v[40:41], v[40:41], v[56:57]
	v_pk_mul_f32 v[38:39], v[38:39], v[44:45]
	v_pk_mul_f32 v[36:37], v[36:37], v[56:57]
	v_cvt_pk_bf16_f32 v44, v40, v41
	v_cvt_pk_bf16_f32 v45, v42, v43
	s_nop 0
	v_cvt_pk_bf16_f32 v46, v36, v37
	v_cvt_pk_bf16_f32 v47, v38, v39
	global_store_dwordx4 v[54:55], v[44:47], off offset:256 sc1
	s_and_saveexec_b64 s[6:7], vcc
	s_cbranch_execz .LBB0_3031
	global_store_dwordx4 v[52:53], v[40:43], off offset:512 sc1
	global_store_dwordx4 v[52:53], v[36:39], off offset:528 sc1

; __device__ __forceinline__ unsigned cvt_pk_bf16(float lo, float hi) { unsigned r; asm volatile("v_cvt_pk_bf16_f32 %0, %1, %2" : "=v"(r) : "v"(lo), "v"(hi)); return r; }
;     __device__ __forceinline__ void operator()(const f32x4 (&acc)[2][2][4][2], const Unit& u, int wr, int wc, int fr, int fq) const {
;     ...
;             for (int m = 0; m < 4; ++m) { const int row = row0 + ai * HALF + m * 16; bf16_t* rowp = G + (size_t)row * 2816 + col0;
;                 float* co = nullptr;
;                 if (row < 32768) { const int t = row & 8191; if (t >= 8190) co = outP + ((size_t)(row >> 13) * 2 + (t - 8190)) * 2816 + col0; }
;                 else { const int i = row & 7; if (i >= 6) co = outS + ((size_t)((row - 32768) >> 3) * 2 + (i - 6)) * 2816 + col0; }
;                 const float rs = rsqrtf(rsv[ai][m] * (1.f / 1024.f) + 1e-6f);
; #pragma unroll
;                 for (int bj = 0; bj < 2; ++bj) { const f32x4 v0 = acc[ai][bj][m][0] * rs, v1 = acc[ai][bj][m][1] * rs;
;                     u32x4 w; w.x = cvt_pk_bf16(v0[0], v0[1]); w.y = cvt_pk_bf16(v0[2], v0[3]); w.z = cvt_pk_bf16(v1[0], v1[1]); w.w = cvt_pk_bf16(v1[2], v1[3]);
;                     *(u32x4*)(rowp + bj * HALF) = w;
;                     if (co) { *(f32x4*)(co + bj * HALF) = v0; *(f32x4*)(co + bj * HALF + 4) = v1; } } }
.LBB0_3039:
	s_or_b64 exec, exec, s[6:7]
	v_fmamk_f32 v39, v135, 0x3a800000, v223
	v_mul_f32_e32 v42, 0x4b800000, v39
	v_cmp_gt_f32_e32 vcc, s53, v39
	v_readlane_b32 s6, v240, 12
	v_readlane_b32 s7, v240, 13
	v_cndmask_b32_e32 v39, v39, v42, vcc
	v_rsq_f32_e32 v42, v39
	v_mov_b64_e32 v[40:41], s[6:7]
	v_mad_i64_i32 v[38:39], s[6:7], v38, s52, v[40:41]
	v_mul_f32_e32 v40, 0x45800000, v42
	v_cndmask_b32_e32 v40, v42, v40, vcc
	v_lshl_add_u64 v[38:39], v[132:133], 1, v[38:39]
	v_cmp_ne_u64_e32 vcc, 0, v[36:37]
	v_pk_mul_f32 v[34:35], v[34:35], v[40:41] op_sel_hi:[1,0]
	v_pk_mul_f32 v[32:33], v[32:33], v[40:41] op_sel_hi:[1,0]
	v_pk_mul_f32 v[30:31], v[30:31], v[40:41] op_sel_hi:[1,0]
	v_pk_mul_f32 v[28:29], v[28:29], v[40:41] op_sel_hi:[1,0]
	v_cvt_pk_bf16_f32 v42, v32, v33
	v_cvt_pk_bf16_f32 v43, v34, v35
	s_nop 0
	v_cvt_pk_bf16_f32 v44, v28, v29
	v_cvt_pk_bf16_f32 v45, v30, v31
	global_store_dwordx4 v[38:39], v[42:45], off sc1
	s_and_saveexec_b64 s[6:7], vcc
	s_cbranch_execz .LBB0_3041
	global_store_dwordx4 v[36:37], v[32:35], off sc1
	global_store_dwordx4 v[36:37], v[28:31], off offset:16 sc1
.LBB0_3041:
	s_or_b64 exec, exec, s[6:7]
	v_mov_b32_e32 v41, v40
	v_mov_b32_e32 v28, v40
	v_mov_b32_e32 v29, v40
	v_pk_mul_f32 v[26:27], v[26:27], v[28:29]
	v_pk_mul_f32 v[24:25], v[24:25], v[40:41]
	v_pk_mul_f32 v[22:23], v[22:23], v[28:29]
	v_pk_mul_f32 v[20:21], v[20:21], v[40:41]
	v_cvt_pk_bf16_f32 v28, v24, v25
	v_cvt_pk_bf16_f32 v29, v26, v27
	s_nop 0
	v_cvt_pk_bf16_f32 v30, v20, v21
	v_cvt_pk_bf16_f32 v31, v22, v23
	global_store_dwordx4 v[38:39], v[28:31], off offset:256 sc1
	s_and_saveexec_b64 s[6:7], vcc
	s_cbranch_execz .LBB0_3043
	global_store_dwordx4 v[36:37], v[24:27], off offset:512 sc1
	global_store_dwordx4 v[36:37], v[20:23], off offset:528 sc1

; __device__ __forceinline__ unsigned cvt_pk_bf16(float lo, float hi) { unsigned r; asm volatile("v_cvt_pk_bf16_f32 %0, %1, %2" : "=v"(r) : "v"(lo), "v"(hi)); return r; }
;     __device__ __forceinline__ void operator()(const f32x4 (&acc)[2][2][4][2], const Unit& u, int wr, int wc, int fr, int fq) const {
;     ...
;             for (int m = 0; m < 4; ++m) { const int row = row0 + ai * HALF + m * 16; bf16_t* rowp = G + (size_t)row * 2816 + col0;
;                 float* co = nullptr;
;                 if (row < 32768) { const int t = row & 8191; if (t >= 8190) co = outP + ((size_t)(row >> 13) * 2 + (t - 8190)) * 2816 + col0; }
;                 else { const int i = row & 7; if (i >= 6) co = outS + ((size_t)((row - 32768) >> 3) * 2 + (i - 6)) * 2816 + col0; }
;                 const float rs = rsqrtf(rsv[ai][m] * (1.f / 1024.f) + 1e-6f);
; #pragma unroll
;                 for (int bj = 0; bj < 2; ++bj) { const f32x4 v0 = acc[ai][bj][m][0] * rs, v1 = acc[ai][bj][m][1] * rs;
;                     u32x4 w; w.x = cvt_pk_bf16(v0[0], v0[1]); w.y = cvt_pk_bf16(v0[2], v0[3]); w.z = cvt_pk_bf16(v1[0], v1[1]); w.w = cvt_pk_bf16(v1[2], v1[3]);
;                     *(u32x4*)(rowp + bj * HALF) = w;
;                     if (co) { *(f32x4*)(co + bj * HALF) = v0; *(f32x4*)(co + bj * HALF + 4) = v1; } } }
.LBB0_3051:
	s_or_b64 exec, exec, s[0:1]
	v_fmamk_f32 v1, v1, 0x3a800000, v223
	v_mul_f32_e32 v3, 0x4b800000, v1
	v_cmp_gt_f32_e32 vcc, s53, v1
	v_readlane_b32 s0, v240, 12
	v_readlane_b32 s1, v240, 13
	v_cndmask_b32_e32 v1, v1, v3, vcc
	v_rsq_f32_e32 v1, v1
	v_mov_b64_e32 v[22:23], s[0:1]
	v_mad_i64_i32 v[2:3], s[0:1], v2, s52, v[22:23]
	v_mul_f32_e32 v22, 0x45800000, v1
	v_cndmask_b32_e32 v22, v1, v22, vcc
	v_lshl_add_u64 v[2:3], v[132:133], 1, v[2:3]
	v_cmp_ne_u64_e32 vcc, 0, v[20:21]
	v_pk_mul_f32 v[18:19], v[18:19], v[22:23] op_sel_hi:[1,0]
	v_pk_mul_f32 v[16:17], v[16:17], v[22:23] op_sel_hi:[1,0]
	v_pk_mul_f32 v[14:15], v[14:15], v[22:23] op_sel_hi:[1,0]
	v_pk_mul_f32 v[12:13], v[12:13], v[22:23] op_sel_hi:[1,0]
	v_cvt_pk_bf16_f32 v24, v16, v17
	v_cvt_pk_bf16_f32 v25, v18, v19
	s_nop 0
	v_cvt_pk_bf16_f32 v26, v12, v13
	v_cvt_pk_bf16_f32 v27, v14, v15
	global_store_dwordx4 v[2:3], v[24:27], off sc1
	s_and_saveexec_b64 s[0:1], vcc
	s_cbranch_execz .LBB0_3053
	global_store_dwordx4 v[20:21], v[16:19], off sc1
	global_store_dwordx4 v[20:21], v[12:15], off offset:16 sc1

;     static __device__ __forceinline__ void unpk4(const u32x2 w, float (&o)[4]) { o[0] = bf_lo(w.x); o[1] = bf_hi(w.x); o[2] = bf_lo(w.y); o[3] = bf_hi(w.y); }
;     template <int N> static __device__ __forceinline__ u32x2 dpp_prev(const u32x2 pv, const u32x2 cur) { u32x2 r; r.x = dpp_prev1<N>(pv.x, cur.x); r.y = dpp_prev1<N>(pv.y, cur.y); return r; }
;     __device__ __forceinline__ void operator()(const f32x4 (&acc)[2][2][4][2], const Unit& u, int wr, int wc, int fr, int fq) const {
;     ...
;         float rs8[2][4];
; #pragma unroll
;         for (int ai = 0; ai < 2; ++ai)
; #pragma unroll
;             for (int m = 0; m < 4; ++m) rs8[ai][m] = rsqrtf(SS[u.rb + (u.half ? 0 : ai * HALF) + wr * 64 + fr + 16 * m] * (1.f / 1024.f) + 1e-6f);
;         if (u.pm < 128) {
;     ...
;         for (int bj = 0; bj < 2; ++bj)
; #pragma unroll
;           for (int hv = 0; hv < 2; ++hv) {
;             const int col = u.pn * BM + bj * HALF + wc * 32 + 8 * fq + 4 * hv;
;             float w0[4], w1[4], w2[4], bb[4];
;             ld4f(cw + col, w0); ld4f(cw + 2816 + col, w1); ld4f(cw + 2 * 2816 + col, w2); ld4f(cb + col, bb);
;             {
;                 const int i = fr & 7;
;                 u32x2 gq[4];
; #pragma unroll
;                 for (int m = 0; m < 4; ++m) { const int row = row0 + m * 16; gq[m] = *(const u32x2*)(G + (size_t)row * 2816 + col); }
; #pragma unroll
;                 for (int mh = 0; mh < 4; mh += 2) {
;                 f32x4 c0[4], c1[4];
; #pragma unroll
;                 for (int m = mh; m < mh + 2; ++m) { const int row = row0 + m * 16; const float* cx = ctx + (size_t)((row - 32768) >> 3) * 2 * 2816 + col;
;                     c0[m] = *(const f32x4*)cx; c1[m] = *(const f32x4*)(cx + 2816); }
; #pragma unroll
;                 for (int m = mh; m < mh + 2; ++m) { const int row = row0 + m * 16; const u32x2 cur = gq[m];
;                     const u32x2 q1 = dpp_prev<1>(cur, cur), q2 = dpp_prev<2>(cur, cur);
;                     float g0[4], g1[4], g2[4]; unpk4(cur, g0); unpk4(q1, g1); unpk4(q2, g2);
; #pragma unroll
;                     for (int j = 0; j < 4; ++j) { const float x1 = c1[m][j], x0 = c0[m][j];
;                         if (i < 1) g1[j] = x1;
;                         if (i < 2) g2[j] = (i == 1) ? x1 : x0; }
.LBB0_3138:
	v_mov_b32_e32 v1, v217
	v_mov_b32_e32 v136, v218
	s_add_i32 s47, s82, s58
	s_cmpk_lt_i32 s79, 0x80
	v_add_u32_e32 v210, s47, v1
	v_ashrrev_i32_e32 v211, 31, v210
	s_waitcnt lgkmcnt(0)
	v_add_u32_e32 v194, 16, v210
	v_add_u32_e32 v192, 32, v210
	v_lshl_add_u64 v[2:3], v[210:211], 2, s[10:11]
	v_ashrrev_i32_e32 v195, 31, v194
	v_ashrrev_i32_e32 v193, 31, v192
	v_add_u32_e32 v190, 48, v210
	global_load_dword v137, v[2:3], off
	v_lshl_add_u64 v[2:3], v[194:195], 2, s[10:11]
	v_lshl_add_u64 v[132:133], v[192:193], 2, s[10:11]
	v_ashrrev_i32_e32 v191, 31, v190
	v_lshl_add_u64 v[134:135], v[190:191], 2, s[10:11]
	global_load_dword v2, v[2:3], off
	s_nop 0
	global_load_dword v132, v[132:133], off
	s_nop 0
	global_load_dword v133, v[134:135], off
	v_lshl_add_u32 v3, v136, 3, s59
	s_waitcnt vmcnt(0)
	v_fmamk_f32 v134, v137, 0x3a800000, v223
	v_mul_f32_e32 v135, 0x4b800000, v134
	v_cmp_gt_f32_e32 vcc, s66, v134
	v_fmamk_f32 v2, v2, 0x3a800000, v223
	v_fmamk_f32 v132, v132, 0x3a800000, v223
	v_fmamk_f32 v133, v133, 0x3a800000, v223
	v_cndmask_b32_e32 v134, v134, v135, vcc
	v_mul_f32_e32 v135, 0x4b800000, v2
	v_mul_f32_e32 v136, 0x4b800000, v132
	v_mul_f32_e32 v137, 0x4b800000, v133
	v_cmp_gt_f32_e64 s[0:1], s66, v2
	v_cmp_gt_f32_e64 s[6:7], s66, v132
	v_cmp_gt_f32_e64 s[8:9], s66, v133
	v_rsq_f32_e32 v134, v134
	v_cndmask_b32_e64 v2, v2, v135, s[0:1]
	v_cndmask_b32_e64 v132, v132, v136, s[6:7]
	v_cndmask_b32_e64 v133, v133, v137, s[8:9]
	v_rsq_f32_e32 v2, v2
	v_rsq_f32_e32 v132, v132
	v_rsq_f32_e32 v133, v133
	v_mul_f32_e32 v135, 0x45800000, v134
	v_cndmask_b32_e32 v188, v134, v135, vcc
	v_mul_f32_e32 v134, 0x45800000, v2
	v_mul_f32_e32 v135, 0x45800000, v132
	v_mul_f32_e32 v136, 0x45800000, v133
	v_cndmask_b32_e64 v186, v2, v134, s[0:1]
	v_cndmask_b32_e64 v184, v132, v135, s[6:7]
	v_cndmask_b32_e64 v2, v133, v136, s[8:9]
	s_mov_b64 s[0:1], -1
	s_cbranch_scc1 .LBB0_3141
	v_lshl_add_u32 v150, s80, 8, v3
	v_ashrrev_i32_e32 v151, 31, v150
	v_readlane_b32 s56, v240, 12
	v_lshlrev_b64 v[160:161], 1, v[150:151]
	v_readlane_b32 s57, v240, 13
	v_add_u32_e32 v134, 0xffff8000, v210
	v_add_u32_e32 v152, 0xffff8010, v210
	v_lshl_add_u64 v[154:155], s[56:57], 0, v[160:161]
	v_mad_i64_i32 v[132:133], s[0:1], v210, s67, v[154:155]
	global_load_dwordx2 v[212:213], v[132:133], off
	v_lshlrev_b64 v[132:133], 2, v[150:151]
	v_lshl_add_u64 v[156:157], s[16:17], 0, v[132:133]
	v_ashrrev_i32_e32 v151, 3, v134
	v_mad_i64_i32 v[134:135], s[0:1], v151, s70, v[156:157]
	v_add_co_u32_e32 v136, vcc, s41, v134
	v_readlane_b32 s0, v240, 58
	s_nop 0
	v_addc_co_u32_e32 v137, vcc, 0, v135, vcc
	global_load_dwordx4 v[168:171], v[134:135], off
	global_load_dwordx4 v[172:175], v[136:137], off offset:3072
	v_lshl_add_u64 v[134:135], s[12:13], 0, v[132:133]
	v_lshl_add_u64 v[136:137], s[14:15], 0, v[132:133]
	global_load_dwordx4 v[140:143], v[134:135], off
	global_load_dwordx4 v[144:147], v[136:137], off
	v_lshl_add_u64 v[134:135], s[18:19], 0, v[132:133]
	global_load_dwordx4 v[136:139], v[134:135], off
	v_lshl_add_u64 v[132:133], s[20:21], 0, v[132:133]
	global_load_dwordx4 v[132:135], v[132:133], off
	v_readlane_b32 s1, v240, 59
	v_ashrrev_i32_e32 v166, 3, v152
	v_and_b32_e32 v167, 7, v1
	v_mov_b64_e32 v[158:159], s[0:1]
	v_mad_i64_i32 v[162:163], s[0:1], v194, s67, v[154:155]
	v_mad_i64_i32 v[164:165], s[0:1], v192, s67, v[154:155]
	v_mad_i64_i32 v[154:155], s[0:1], v190, s67, v[154:155]
	v_mad_i64_i32 v[176:177], s[0:1], v166, s70, v[156:157]
	global_load_dwordx2 v[226:227], v[162:163], off
	s_nop 0
	global_load_dwordx2 v[164:165], v[164:165], off
	s_nop 0
	global_load_dwordx2 v[162:163], v[154:155], off
	v_add_co_u32_e32 v154, vcc, s41, v176
	v_mad_i64_i32 v[152:153], s[0:1], v210, s67, v[158:159]
	s_nop 0
	v_addc_co_u32_e32 v155, vcc, 0, v177, vcc
	global_load_dwordx4 v[176:179], v[176:177], off
	s_nop 0
	global_load_dwordx4 v[180:183], v[154:155], off offset:3072
	v_cmp_eq_u32_e32 vcc, 1, v167
	v_cmp_eq_u32_e64 s[6:7], 0, v167
	v_cmp_gt_u32_e64 s[0:1], 2, v167
	v_mov_b64_e32 v[148:149], s[30:31]
	v_lshl_add_u64 v[214:215], v[152:153], 0, v[160:161]
	s_waitcnt vmcnt(11)
	v_mov_b32_dpp v185, v212 row_ror:1 row_mask:0xf bank_mask:0xf bound_ctrl:1
	v_mov_b32_dpp v187, v213 row_ror:1 row_mask:0xf bank_mask:0xf bound_ctrl:1
	v_mov_b32_dpp v189, v212 row_ror:2 row_mask:0xf bank_mask:0xf bound_ctrl:1
	v_mov_b32_dpp v185, v212 row_shr:1 row_mask:0xf bank_mask:0xf
	v_mov_b32_dpp v187, v213 row_shr:1 row_mask:0xf bank_mask:0xf
	v_mov_b32_dpp v189, v212 row_shr:2 row_mask:0xf bank_mask:0xf
	v_lshlrev_b32_e32 v154, 16, v212
	v_and_b32_e32 v155, 0xffff0000, v212
	v_mov_b32_dpp v191, v213 row_ror:2 row_mask:0xf bank_mask:0xf bound_ctrl:1
	s_waitcnt vmcnt(9)
	v_cndmask_b32_e32 v193, v168, v172, vcc
	v_cndmask_b32_e32 v195, v169, v173, vcc
	v_cndmask_b32_e32 v211, v170, v174, vcc
	v_cndmask_b32_e32 v212, v171, v175, vcc
	v_lshlrev_b32_e32 v168, 16, v185
	v_and_b32_e32 v169, 0xffff0000, v185
	v_lshlrev_b32_e32 v170, 16, v187
	v_and_b32_e32 v171, 0xffff0000, v187
	v_lshlrev_b32_e32 v185, 16, v189
	v_and_b32_e32 v187, 0xffff0000, v189
	v_cndmask_b32_e64 v171, v171, v175, s[6:7]
	v_cndmask_b32_e64 v170, v170, v174, s[6:7]
	v_cndmask_b32_e64 v175, v187, v195, s[0:1]
	v_cndmask_b32_e64 v174, v185, v193, s[0:1]
	v_cndmask_b32_e64 v169, v169, v173, s[6:7]
	v_cndmask_b32_e64 v168, v168, v172, s[6:7]
	s_waitcnt vmcnt(7)
	v_pk_fma_f32 v[174:175], v[140:141], v[174:175], v[144:145]
	v_mov_b32_dpp v191, v213 row_shr:2 row_mask:0xf bank_mask:0xf
	s_waitcnt vmcnt(6)
	v_pk_fma_f32 v[168:169], v[136:137], v[168:169], v[174:175]
	v_lshlrev_b32_e32 v189, 16, v191
	v_and_b32_e32 v191, 0xffff0000, v191
	s_waitcnt vmcnt(5)
; __device__ __forceinline__ unsigned cvt_pk_bf16(float lo, float hi) { unsigned r; asm volatile("v_cvt_pk_bf16_f32 %0, %1, %2" : "=v"(r) : "v"(lo), "v"(hi)); return r; }
;     static __device__ __forceinline__ void unpk4(const u32x2 w, float (&o)[4]) { o[0] = bf_lo(w.x); o[1] = bf_hi(w.x); o[2] = bf_lo(w.y); o[3] = bf_hi(w.y); }
;     template <int N> static __device__ __forceinline__ u32x2 dpp_prev(const u32x2 pv, const u32x2 cur) { u32x2 r; r.x = dpp_prev1<N>(pv.x, cur.x); r.y = dpp_prev1<N>(pv.y, cur.y); return r; }
;     static __device__ __forceinline__ void finish(const float (&g0)[4], const float (&g1)[4], const float (&g2)[4], const float (&w0)[4], const float (&w1)[4], const float (&w2)[4], const float (&bb)[4],
;                                                   const f32x4 v, float rs, bf16_t* dst) {
;         float h[4];
; #pragma unroll
;         for (int j = 0; j < 4; j += 2) {
;             const f32x2 gc = (f32x2){bb[j] + w0[j] * g2[j] + w1[j] * g1[j] + w2[j] * g0[j], bb[j + 1] + w0[j + 1] * g2[j + 1] + w1[j + 1] * g1[j + 1] + w2[j + 1] * g0[j + 1]};
;             const f32x2 ge = gelu_pk(gc); h[j] = ge.x * v[j] * rs; h[j + 1] = ge.y * v[j + 1] * rs; }
;         u32x2 w; w.x = cvt_pk_bf16(h[0], h[1]); w.y = cvt_pk_bf16(h[2], h[3]);
;         *(u32x2*)dst = w;
;     }
;     __device__ __forceinline__ void operator()(const f32x4 (&acc)[2][2][4][2], const Unit& u, int wr, int wc, int fr, int fq) const {
;     ...
;                 for (int m = mh; m < mh + 2; ++m) { const int row = row0 + m * 16; const u32x2 cur = gq[m];
;                     const u32x2 q1 = dpp_prev<1>(cur, cur), q2 = dpp_prev<2>(cur, cur);
;                     float g0[4], g1[4], g2[4]; unpk4(cur, g0); unpk4(q1, g1); unpk4(q2, g2);
; #pragma unroll
;                     for (int j = 0; j < 4; ++j) { const float x1 = c1[m][j], x0 = c0[m][j];
;                         if (i < 1) g1[j] = x1;
;                         if (i < 2) g2[j] = (i == 1) ? x1 : x0; }
;                     finish(g0, g1, g2, w0, w1, w2, bb, acc[0][bj][m][hv], rs8[0][m], H + (size_t)row * 2816 + col); }
	v_pk_fma_f32 v[154:155], v[132:133], v[154:155], v[168:169]
	v_cndmask_b32_e64 v173, v191, v212, s[0:1]
	v_cndmask_b32_e64 v172, v189, v211, s[0:1]
	v_pk_mul_f32 v[168:169], v[154:155], s[26:27] op_sel_hi:[1,0]
	v_pk_fma_f32 v[172:173], v[142:143], v[172:173], v[146:147]
	v_med3_f32 v168, v168, s71, v224
	v_med3_f32 v169, v169, s71, v224
	v_pk_fma_f32 v[170:171], v[138:139], v[170:171], v[172:173]
	v_pk_mul_f32 v[172:173], v[168:169], v[168:169]
	v_pk_mul_f32 v[154:155], v[154:155], 0.5 op_sel_hi:[1,0]
	v_pk_fma_f32 v[174:175], v[172:173], s[28:29], v[148:149] op_sel_hi:[1,0,0] neg_lo:[1,0,0] neg_hi:[1,0,0]
	s_nop 0
	v_pk_fma_f32 v[174:175], v[172:173], v[174:175], s[34:35] op_sel_hi:[1,1,0]
	s_nop 0
	v_pk_fma_f32 v[174:175], v[172:173], v[174:175], s[36:37] op_sel_hi:[1,1,0]
	s_nop 0
	v_pk_fma_f32 v[174:175], v[172:173], v[174:175], s[38:39] op_sel_hi:[1,1,0]
	s_nop 0
	v_pk_fma_f32 v[174:175], v[172:173], v[174:175], s[40:41] op_sel_hi:[1,1,0]
	s_nop 0
	v_pk_fma_f32 v[174:175], v[172:173], v[174:175], s[42:43] op_sel_hi:[1,1,0]
	s_nop 0
	v_pk_fma_f32 v[172:173], v[172:173], v[174:175], s[44:45] op_sel_hi:[1,1,0]
	s_nop 0
	v_pk_mul_f32 v[168:169], v[168:169], v[172:173]
	s_nop 0
	v_pk_fma_f32 v[154:155], v[154:155], v[168:169], v[154:155]
	s_nop 0
	v_mul_f32_e32 v154, v128, v154
	v_mul_f32_e32 v167, v188, v154
	v_mul_f32_e32 v154, v129, v155
	v_mul_f32_e32 v174, v188, v154
	v_lshlrev_b32_e32 v154, 16, v213
	v_and_b32_e32 v155, 0xffff0000, v213
	v_pk_fma_f32 v[154:155], v[134:135], v[154:155], v[170:171]
	s_nop 0
	v_pk_mul_f32 v[168:169], v[154:155], s[26:27] op_sel_hi:[1,0]
	v_pk_mul_f32 v[154:155], v[154:155], 0.5 op_sel_hi:[1,0]
	v_med3_f32 v168, v168, s71, v224
	v_med3_f32 v169, v169, s71, v224
	v_pk_mul_f32 v[170:171], v[168:169], v[168:169]
	s_nop 0
	v_pk_fma_f32 v[172:173], v[170:171], s[28:29], v[148:149] op_sel_hi:[1,0,0] neg_lo:[1,0,0] neg_hi:[1,0,0]
	s_nop 0
	v_pk_fma_f32 v[172:173], v[170:171], v[172:173], s[34:35] op_sel_hi:[1,1,0]
	s_nop 0
	v_pk_fma_f32 v[172:173], v[170:171], v[172:173], s[36:37] op_sel_hi:[1,1,0]
	s_nop 0
	v_pk_fma_f32 v[172:173], v[170:171], v[172:173], s[38:39] op_sel_hi:[1,1,0]
	s_nop 0
	v_pk_fma_f32 v[172:173], v[170:171], v[172:173], s[40:41] op_sel_hi:[1,1,0]
	s_nop 0
	v_pk_fma_f32 v[172:173], v[170:171], v[172:173], s[42:43] op_sel_hi:[1,1,0]
	s_nop 0
	v_pk_fma_f32 v[170:171], v[170:171], v[172:173], s[44:45] op_sel_hi:[1,1,0]
	s_nop 0
	v_pk_mul_f32 v[168:169], v[168:169], v[170:171]
	s_nop 0
	v_pk_fma_f32 v[154:155], v[154:155], v[168:169], v[154:155]
	s_nop 0
	v_mul_f32_e32 v154, v130, v154
	v_mul_f32_e32 v168, v188, v154
	v_mul_f32_e32 v154, v131, v155
	v_mul_f32_e32 v155, v188, v154
	v_cvt_pk_bf16_f32 v154, v167, v174
	v_cvt_pk_bf16_f32 v155, v168, v155
	global_store_dwordx2 v[214:215], v[154:155], off sc1
	s_waitcnt vmcnt(5)
	v_mov_b32_dpp v167, v226 row_ror:2 row_mask:0xf bank_mask:0xf bound_ctrl:1
	v_mov_b32_dpp v154, v226 row_ror:1 row_mask:0xf bank_mask:0xf bound_ctrl:1
	v_mov_b32_dpp v155, v227 row_ror:1 row_mask:0xf bank_mask:0xf bound_ctrl:1
	v_mov_b32_dpp v168, v227 row_ror:2 row_mask:0xf bank_mask:0xf bound_ctrl:1
	v_mov_b32_dpp v154, v226 row_shr:1 row_mask:0xf bank_mask:0xf
	v_mov_b32_dpp v155, v227 row_shr:1 row_mask:0xf bank_mask:0xf
	v_mov_b32_dpp v167, v226 row_shr:2 row_mask:0xf bank_mask:0xf
	v_mov_b32_dpp v168, v227 row_shr:2 row_mask:0xf bank_mask:0xf
	v_lshlrev_b32_e32 v170, 16, v154
	v_and_b32_e32 v154, 0xffff0000, v154
	v_lshlrev_b32_e32 v172, 16, v155
	v_and_b32_e32 v155, 0xffff0000, v155
	v_lshlrev_b32_e32 v174, 16, v167
	v_and_b32_e32 v167, 0xffff0000, v167
	v_lshlrev_b32_e32 v175, 16, v168
	v_and_b32_e32 v173, 0xffff0000, v168
	s_waitcnt vmcnt(1)
	v_cndmask_b32_e64 v169, v154, v181, s[6:7]
	v_cndmask_b32_e64 v168, v170, v180, s[6:7]
	v_cndmask_b32_e64 v171, v155, v183, s[6:7]
	v_cndmask_b32_e64 v170, v172, v182, s[6:7]
	v_cndmask_b32_e32 v154, v176, v180, vcc
	v_cndmask_b32_e32 v155, v177, v181, vcc
	v_cndmask_b32_e32 v172, v178, v182, vcc
	v_cndmask_b32_e64 v172, v175, v172, s[0:1]
	v_cndmask_b32_e64 v175, v167, v155, s[0:1]
	v_cndmask_b32_e64 v174, v174, v154, s[0:1]
	v_cndmask_b32_e32 v176, v179, v183, vcc
	v_pk_fma_f32 v[174:175], v[140:141], v[174:175], v[144:145]
	v_cndmask_b32_e64 v173, v173, v176, s[0:1]
	v_lshlrev_b32_e32 v178, 16, v226
	v_and_b32_e32 v179, 0xffff0000, v226
	v_pk_fma_f32 v[168:169], v[136:137], v[168:169], v[174:175]
	v_pk_fma_f32 v[172:173], v[142:143], v[172:173], v[146:147]
	v_pk_fma_f32 v[168:169], v[132:133], v[178:179], v[168:169]
	v_pk_fma_f32 v[170:171], v[138:139], v[170:171], v[172:173]
	v_pk_mul_f32 v[172:173], v[168:169], s[26:27] op_sel_hi:[1,0]
	v_pk_mul_f32 v[168:169], v[168:169], 0.5 op_sel_hi:[1,0]
	v_med3_f32 v172, v172, s71, v224
	v_med3_f32 v173, v173, s71, v224
	v_pk_mul_f32 v[174:175], v[172:173], v[172:173]
	v_mad_i64_i32 v[154:155], s[8:9], v194, s67, v[158:159]
	v_pk_fma_f32 v[178:179], v[174:175], s[28:29], v[148:149] op_sel_hi:[1,0,0] neg_lo:[1,0,0] neg_hi:[1,0,0]
	v_lshl_add_u64 v[176:177], v[154:155], 0, v[160:161]
	v_pk_fma_f32 v[178:179], v[174:175], v[178:179], s[34:35] op_sel_hi:[1,1,0]
	s_nop 0
	v_pk_fma_f32 v[178:179], v[174:175], v[178:179], s[36:37] op_sel_hi:[1,1,0]
	s_nop 0
	v_pk_fma_f32 v[178:179], v[174:175], v[178:179], s[38:39] op_sel_hi:[1,1,0]
	s_nop 0
	v_pk_fma_f32 v[178:179], v[174:175], v[178:179], s[40:41] op_sel_hi:[1,1,0]
	s_nop 0
	v_pk_fma_f32 v[178:179], v[174:175], v[178:179], s[42:43] op_sel_hi:[1,1,0]
	s_nop 0
	v_pk_fma_f32 v[174:175], v[174:175], v[178:179], s[44:45] op_sel_hi:[1,1,0]
	s_nop 0
	v_pk_mul_f32 v[172:173], v[172:173], v[174:175]
	s_nop 0
	v_pk_fma_f32 v[168:169], v[168:169], v[172:173], v[168:169]
; __device__ __forceinline__ unsigned cvt_pk_bf16(float lo, float hi) { unsigned r; asm volatile("v_cvt_pk_bf16_f32 %0, %1, %2" : "=v"(r) : "v"(lo), "v"(hi)); return r; }
;     static __device__ __forceinline__ void finish(const float (&g0)[4], const float (&g1)[4], const float (&g2)[4], const float (&w0)[4], const float (&w1)[4], const float (&w2)[4], const float (&bb)[4],
;                                                   const f32x4 v, float rs, bf16_t* dst) {
;         float h[4];
; #pragma unroll
;         for (int j = 0; j < 4; j += 2) {
;             const f32x2 gc = (f32x2){bb[j] + w0[j] * g2[j] + w1[j] * g1[j] + w2[j] * g0[j], bb[j + 1] + w0[j + 1] * g2[j + 1] + w1[j + 1] * g1[j + 1] + w2[j + 1] * g0[j + 1]};
;             const f32x2 ge = gelu_pk(gc); h[j] = ge.x * v[j] * rs; h[j + 1] = ge.y * v[j + 1] * rs; }
;         u32x2 w; w.x = cvt_pk_bf16(h[0], h[1]); w.y = cvt_pk_bf16(h[2], h[3]);
;         *(u32x2*)dst = w;
;     }
;     __device__ __forceinline__ void operator()(const f32x4 (&acc)[2][2][4][2], const Unit& u, int wr, int wc, int fr, int fq) const {
;     ...
;                 u32x2 gq[4];
; #pragma unroll
;                 for (int m = 0; m < 4; ++m) { const int row = row0 + m * 16; gq[m] = *(const u32x2*)(G + (size_t)row * 2816 + col); }
; #pragma unroll
;                 for (int mh = 0; mh < 4; mh += 2) {
;                 f32x4 c0[4], c1[4];
; #pragma unroll
;                 for (int m = mh; m < mh + 2; ++m) { const int row = row0 + m * 16; const float* cx = ctx + (size_t)((row - 32768) >> 3) * 2 * 2816 + col;
;                     c0[m] = *(const f32x4*)cx; c1[m] = *(const f32x4*)(cx + 2816); }
; #pragma unroll
;                 for (int m = mh; m < mh + 2; ++m) { const int row = row0 + m * 16; const u32x2 cur = gq[m];
;                     const u32x2 q1 = dpp_prev<1>(cur, cur), q2 = dpp_prev<2>(cur, cur);
;                     float g0[4], g1[4], g2[4]; unpk4(cur, g0); unpk4(q1, g1); unpk4(q2, g2);
; #pragma unroll
;                     for (int j = 0; j < 4; ++j) { const float x1 = c1[m][j], x0 = c0[m][j];
;                         if (i < 1) g1[j] = x1;
;                         if (i < 2) g2[j] = (i == 1) ? x1 : x0; }
;                     finish(g0, g1, g2, w0, w1, w2, bb, acc[0][bj][m][hv], rs8[0][m], H + (size_t)row * 2816 + col); }
	s_nop 0
	v_mul_f32_e32 v167, v120, v168
	v_mul_f32_e32 v168, v121, v169
	v_mul_f32_e32 v178, v186, v168
	v_lshlrev_b32_e32 v168, 16, v227
	v_and_b32_e32 v169, 0xffff0000, v227
	v_pk_fma_f32 v[168:169], v[134:135], v[168:169], v[170:171]
	v_mul_f32_e32 v167, v186, v167
	v_pk_mul_f32 v[170:171], v[168:169], s[26:27] op_sel_hi:[1,0]
	v_pk_mul_f32 v[168:169], v[168:169], 0.5 op_sel_hi:[1,0]
	v_med3_f32 v170, v170, s71, v224
	v_med3_f32 v171, v171, s71, v224
	v_pk_mul_f32 v[172:173], v[170:171], v[170:171]
	s_nop 0
	v_pk_fma_f32 v[174:175], v[172:173], s[28:29], v[148:149] op_sel_hi:[1,0,0] neg_lo:[1,0,0] neg_hi:[1,0,0]
	s_nop 0
	v_pk_fma_f32 v[174:175], v[172:173], v[174:175], s[34:35] op_sel_hi:[1,1,0]
	s_nop 0
	v_pk_fma_f32 v[174:175], v[172:173], v[174:175], s[36:37] op_sel_hi:[1,1,0]
	s_nop 0
	v_pk_fma_f32 v[174:175], v[172:173], v[174:175], s[38:39] op_sel_hi:[1,1,0]
	s_nop 0
	v_pk_fma_f32 v[174:175], v[172:173], v[174:175], s[40:41] op_sel_hi:[1,1,0]
	s_nop 0
	v_pk_fma_f32 v[174:175], v[172:173], v[174:175], s[42:43] op_sel_hi:[1,1,0]
	s_nop 0
	v_pk_fma_f32 v[172:173], v[172:173], v[174:175], s[44:45] op_sel_hi:[1,1,0]
	s_nop 0
	v_pk_mul_f32 v[170:171], v[170:171], v[172:173]
	s_nop 0
	v_pk_fma_f32 v[168:169], v[168:169], v[170:171], v[168:169]
	s_nop 0
	v_mul_f32_e32 v168, v122, v168
	v_mul_f32_e32 v170, v186, v168
	v_mul_f32_e32 v168, v123, v169
	v_mul_f32_e32 v169, v186, v168
	v_cvt_pk_bf16_f32 v168, v167, v178
	v_add_u32_e32 v167, 0xffff8020, v210
	v_cvt_pk_bf16_f32 v169, v170, v169
	v_ashrrev_i32_e32 v167, 3, v167
	global_store_dwordx2 v[176:177], v[168:169], off sc1
	v_mad_i64_i32 v[168:169], s[8:9], v167, s70, v[156:157]
	v_add_co_u32_e64 v170, s[8:9], s41, v168
	s_nop 1
	v_addc_co_u32_e64 v171, s[8:9], 0, v169, s[8:9]
	global_load_dwordx4 v[170:173], v[170:171], off offset:3072
	s_nop 0
	global_load_dwordx4 v[174:177], v[168:169], off
	v_add_u32_e32 v168, 0xffff8030, v210
	v_ashrrev_i32_e32 v168, 3, v168
	v_mad_i64_i32 v[156:157], s[8:9], v168, s70, v[156:157]
	v_add_co_u32_e64 v182, s[8:9], s41, v156
	v_mov_b32_dpp v169, v164 row_ror:2 row_mask:0xf bank_mask:0xf bound_ctrl:1
	s_nop 0
	v_addc_co_u32_e64 v183, s[8:9], 0, v157, s[8:9]
	global_load_dwordx4 v[178:181], v[156:157], off
	global_load_dwordx4 v[212:215], v[182:183], off offset:3072
	v_mov_b32_dpp v156, v164 row_ror:1 row_mask:0xf bank_mask:0xf bound_ctrl:1
	v_mov_b32_dpp v157, v165 row_ror:1 row_mask:0xf bank_mask:0xf bound_ctrl:1
	v_mov_b32_dpp v169, v164 row_shr:2 row_mask:0xf bank_mask:0xf
	v_mov_b32_dpp v156, v164 row_shr:1 row_mask:0xf bank_mask:0xf
	v_mov_b32_dpp v157, v165 row_shr:1 row_mask:0xf bank_mask:0xf
	v_mov_b32_dpp v182, v165 row_ror:2 row_mask:0xf bank_mask:0xf bound_ctrl:1
	v_lshlrev_b32_e32 v185, 16, v156
	v_and_b32_e32 v156, 0xffff0000, v156
	v_lshlrev_b32_e32 v187, 16, v157
	v_and_b32_e32 v157, 0xffff0000, v157
	v_mov_b32_dpp v182, v165 row_shr:2 row_mask:0xf bank_mask:0xf
	v_lshlrev_b32_e32 v189, 16, v169
	v_and_b32_e32 v169, 0xffff0000, v169
	v_lshlrev_b32_e32 v191, 16, v182
	v_and_b32_e32 v193, 0xffff0000, v182
	s_waitcnt vmcnt(3)
	v_cndmask_b32_e64 v183, v156, v171, s[6:7]
	v_cndmask_b32_e64 v227, v157, v173, s[6:7]
	s_waitcnt vmcnt(2)
	v_cndmask_b32_e32 v156, v174, v170, vcc
	v_cndmask_b32_e32 v157, v175, v171, vcc
	v_cndmask_b32_e64 v182, v185, v170, s[6:7]
	v_cndmask_b32_e64 v226, v187, v172, s[6:7]
	v_cndmask_b32_e32 v170, v176, v172, vcc
	v_cndmask_b32_e32 v171, v177, v173, vcc
	v_cndmask_b32_e64 v173, v169, v157, s[0:1]
	v_cndmask_b32_e64 v172, v189, v156, s[0:1]
	v_pk_fma_f32 v[172:173], v[140:141], v[172:173], v[144:145]
	v_lshlrev_b32_e32 v176, 16, v164
	v_and_b32_e32 v177, 0xffff0000, v164
	v_pk_fma_f32 v[172:173], v[136:137], v[182:183], v[172:173]
	v_cndmask_b32_e64 v171, v193, v171, s[0:1]
	v_pk_fma_f32 v[172:173], v[132:133], v[176:177], v[172:173]
	v_cndmask_b32_e64 v170, v191, v170, s[0:1]
	v_pk_mul_f32 v[176:177], v[172:173], s[26:27] op_sel_hi:[1,0]
	v_pk_fma_f32 v[170:171], v[142:143], v[170:171], v[146:147]
	v_med3_f32 v176, v176, s71, v224
	v_med3_f32 v177, v177, s71, v224
	v_pk_mul_f32 v[182:183], v[176:177], v[176:177]
	v_pk_fma_f32 v[170:171], v[138:139], v[226:227], v[170:171]
	v_pk_fma_f32 v[226:227], v[182:183], s[28:29], v[148:149] op_sel_hi:[1,0,0] neg_lo:[1,0,0] neg_hi:[1,0,0]
	v_pk_mul_f32 v[172:173], v[172:173], 0.5 op_sel_hi:[1,0]
	v_pk_fma_f32 v[226:227], v[182:183], v[226:227], s[34:35] op_sel_hi:[1,1,0]
	v_mad_i64_i32 v[156:157], s[8:9], v192, s67, v[158:159]
	v_pk_fma_f32 v[226:227], v[182:183], v[226:227], s[36:37] op_sel_hi:[1,1,0]
	v_lshl_add_u64 v[174:175], v[156:157], 0, v[160:161]
	v_pk_fma_f32 v[226:227], v[182:183], v[226:227], s[38:39] op_sel_hi:[1,1,0]
	v_mad_i64_i32 v[158:159], s[8:9], v190, s67, v[158:159]
	v_pk_fma_f32 v[226:227], v[182:183], v[226:227], s[40:41] op_sel_hi:[1,1,0]
	v_lshl_add_u64 v[160:161], v[158:159], 0, v[160:161]
	v_pk_fma_f32 v[226:227], v[182:183], v[226:227], s[42:43] op_sel_hi:[1,1,0]
	s_nop 0
	v_pk_fma_f32 v[182:183], v[182:183], v[226:227], s[44:45] op_sel_hi:[1,1,0]
	s_nop 0
	v_pk_mul_f32 v[176:177], v[176:177], v[182:183]
	s_nop 0
	v_pk_fma_f32 v[172:173], v[172:173], v[176:177], v[172:173]
	s_nop 0
	v_mul_f32_e32 v164, v112, v172
	v_mul_f32_e32 v169, v184, v164
	v_mul_f32_e32 v164, v113, v173
	v_mul_f32_e32 v182, v184, v164
	v_lshlrev_b32_e32 v164, 16, v165
	v_and_b32_e32 v165, 0xffff0000, v165
	v_pk_fma_f32 v[164:165], v[134:135], v[164:165], v[170:171]
	s_nop 0
	v_pk_mul_f32 v[170:171], v[164:165], s[26:27] op_sel_hi:[1,0]
	v_pk_mul_f32 v[164:165], v[164:165], 0.5 op_sel_hi:[1,0]
	v_med3_f32 v170, v170, s71, v224
	v_med3_f32 v171, v171, s71, v224
	v_pk_mul_f32 v[172:173], v[170:171], v[170:171]
	s_nop 0
	v_pk_fma_f32 v[176:177], v[172:173], s[28:29], v[148:149] op_sel_hi:[1,0,0] neg_lo:[1,0,0] neg_hi:[1,0,0]
	s_nop 0
	v_pk_fma_f32 v[176:177], v[172:173], v[176:177], s[34:35] op_sel_hi:[1,1,0]
	s_nop 0
	v_pk_fma_f32 v[176:177], v[172:173], v[176:177], s[36:37] op_sel_hi:[1,1,0]
	s_nop 0
	v_pk_fma_f32 v[176:177], v[172:173], v[176:177], s[38:39] op_sel_hi:[1,1,0]
	s_nop 0
	v_pk_fma_f32 v[176:177], v[172:173], v[176:177], s[40:41] op_sel_hi:[1,1,0]
	s_nop 0
	v_pk_fma_f32 v[176:177], v[172:173], v[176:177], s[42:43] op_sel_hi:[1,1,0]
	s_nop 0
	v_pk_fma_f32 v[172:173], v[172:173], v[176:177], s[44:45] op_sel_hi:[1,1,0]
	s_waitcnt vmcnt(0)
; __device__ __forceinline__ unsigned cvt_pk_bf16(float lo, float hi) { unsigned r; asm volatile("v_cvt_pk_bf16_f32 %0, %1, %2" : "=v"(r) : "v"(lo), "v"(hi)); return r; }
;     static __device__ __forceinline__ void finish(const float (&g0)[4], const float (&g1)[4], const float (&g2)[4], const float (&w0)[4], const float (&w1)[4], const float (&w2)[4], const float (&bb)[4],
;                                                   const f32x4 v, float rs, bf16_t* dst) {
;         float h[4];
; #pragma unroll
;         for (int j = 0; j < 4; j += 2) {
;             const f32x2 gc = (f32x2){bb[j] + w0[j] * g2[j] + w1[j] * g1[j] + w2[j] * g0[j], bb[j + 1] + w0[j + 1] * g2[j + 1] + w1[j + 1] * g1[j + 1] + w2[j + 1] * g0[j + 1]};
;             const f32x2 ge = gelu_pk(gc); h[j] = ge.x * v[j] * rs; h[j + 1] = ge.y * v[j + 1] * rs; }
;         u32x2 w; w.x = cvt_pk_bf16(h[0], h[1]); w.y = cvt_pk_bf16(h[2], h[3]);
;         *(u32x2*)dst = w;
;     }
;     __device__ __forceinline__ void operator()(const f32x4 (&acc)[2][2][4][2], const Unit& u, int wr, int wc, int fr, int fq) const {
;     ...
;                 u32x2 gq[4];
; #pragma unroll
;                 for (int m = 0; m < 4; ++m) { const int row = row0 + m * 16; gq[m] = *(const u32x2*)(G + (size_t)row * 2816 + col); }
; #pragma unroll
;                 for (int mh = 0; mh < 4; mh += 2) {
;                 f32x4 c0[4], c1[4];
; #pragma unroll
;                 for (int m = mh; m < mh + 2; ++m) { const int row = row0 + m * 16; const float* cx = ctx + (size_t)((row - 32768) >> 3) * 2 * 2816 + col;
;                     c0[m] = *(const f32x4*)cx; c1[m] = *(const f32x4*)(cx + 2816); }
; #pragma unroll
;                 for (int m = mh; m < mh + 2; ++m) { const int row = row0 + m * 16; const u32x2 cur = gq[m];
;                     const u32x2 q1 = dpp_prev<1>(cur, cur), q2 = dpp_prev<2>(cur, cur);
;                     float g0[4], g1[4], g2[4]; unpk4(cur, g0); unpk4(q1, g1); unpk4(q2, g2);
; #pragma unroll
;                     for (int j = 0; j < 4; ++j) { const float x1 = c1[m][j], x0 = c0[m][j];
;                         if (i < 1) g1[j] = x1;
;                         if (i < 2) g2[j] = (i == 1) ? x1 : x0; }
;                     finish(g0, g1, g2, w0, w1, w2, bb, acc[0][bj][m][hv], rs8[0][m], H + (size_t)row * 2816 + col); }
;                 }
	v_cndmask_b32_e32 v177, v178, v212, vcc
	v_pk_mul_f32 v[170:171], v[170:171], v[172:173]
	v_cndmask_b32_e32 v178, v179, v213, vcc
	v_pk_fma_f32 v[164:165], v[164:165], v[170:171], v[164:165]
	s_nop 0
	v_mul_f32_e32 v164, v114, v164
	v_mul_f32_e32 v170, v184, v164
	v_mul_f32_e32 v164, v115, v165
	v_mul_f32_e32 v165, v184, v164
	v_cvt_pk_bf16_f32 v164, v169, v182
	v_cvt_pk_bf16_f32 v165, v170, v165
	global_store_dwordx2 v[174:175], v[164:165], off sc1
	v_mov_b32_dpp v169, v162 row_ror:2 row_mask:0xf bank_mask:0xf bound_ctrl:1
	v_mov_b32_dpp v165, v163 row_ror:1 row_mask:0xf bank_mask:0xf bound_ctrl:1
	v_mov_b32_dpp v170, v163 row_ror:2 row_mask:0xf bank_mask:0xf bound_ctrl:1
	v_mov_b32_dpp v164, v162 row_ror:1 row_mask:0xf bank_mask:0xf bound_ctrl:1
	v_mov_b32_dpp v165, v163 row_shr:1 row_mask:0xf bank_mask:0xf
	v_mov_b32_dpp v169, v162 row_shr:2 row_mask:0xf bank_mask:0xf
	v_mov_b32_dpp v170, v163 row_shr:2 row_mask:0xf bank_mask:0xf
	v_lshlrev_b32_e32 v172, 16, v165
	v_mov_b32_dpp v164, v162 row_shr:1 row_mask:0xf bank_mask:0xf
	v_lshlrev_b32_e32 v174, 16, v169
	v_and_b32_e32 v169, 0xffff0000, v169
	v_lshlrev_b32_e32 v175, 16, v170
	v_and_b32_e32 v176, 0xffff0000, v170
	v_cndmask_b32_e64 v170, v172, v214, s[6:7]
	v_cndmask_b32_e32 v172, v180, v214, vcc
	v_lshlrev_b32_e32 v171, 16, v164
	v_and_b32_e32 v164, 0xffff0000, v164
	v_and_b32_e32 v173, 0xffff0000, v165
	v_cndmask_b32_e64 v172, v175, v172, s[0:1]
	v_cndmask_b32_e64 v175, v169, v178, s[0:1]
	v_cndmask_b32_e64 v174, v174, v177, s[0:1]
	v_cndmask_b32_e64 v165, v164, v213, s[6:7]
	v_cndmask_b32_e64 v164, v171, v212, s[6:7]
	v_cndmask_b32_e64 v171, v173, v215, s[6:7]
	v_cndmask_b32_e32 v173, v181, v215, vcc
	v_pk_fma_f32 v[140:141], v[140:141], v[174:175], v[144:145]
	v_cndmask_b32_e64 v173, v176, v173, s[0:1]
	v_lshlrev_b32_e32 v176, 16, v162
	v_and_b32_e32 v177, 0xffff0000, v162
	v_pk_fma_f32 v[136:137], v[136:137], v[164:165], v[140:141]
	v_pk_fma_f32 v[142:143], v[142:143], v[172:173], v[146:147]
	v_pk_fma_f32 v[132:133], v[132:133], v[176:177], v[136:137]
	v_pk_fma_f32 v[138:139], v[138:139], v[170:171], v[142:143]
	v_pk_mul_f32 v[136:137], v[132:133], s[26:27] op_sel_hi:[1,0]
	v_pk_mul_f32 v[132:133], v[132:133], 0.5 op_sel_hi:[1,0]
	v_med3_f32 v136, v136, s71, v224
	v_med3_f32 v137, v137, s71, v224
	v_pk_mul_f32 v[140:141], v[136:137], v[136:137]
	s_nop 0
	v_pk_fma_f32 v[142:143], v[140:141], s[28:29], v[148:149] op_sel_hi:[1,0,0] neg_lo:[1,0,0] neg_hi:[1,0,0]
	s_nop 0
	v_pk_fma_f32 v[142:143], v[140:141], v[142:143], s[34:35] op_sel_hi:[1,1,0]
	s_nop 0
	v_pk_fma_f32 v[142:143], v[140:141], v[142:143], s[36:37] op_sel_hi:[1,1,0]
	s_nop 0
	v_pk_fma_f32 v[142:143], v[140:141], v[142:143], s[38:39] op_sel_hi:[1,1,0]
	s_nop 0
	v_pk_fma_f32 v[142:143], v[140:141], v[142:143], s[40:41] op_sel_hi:[1,1,0]
	s_nop 0
	v_pk_fma_f32 v[142:143], v[140:141], v[142:143], s[42:43] op_sel_hi:[1,1,0]
	s_nop 0
	v_pk_fma_f32 v[140:141], v[140:141], v[142:143], s[44:45] op_sel_hi:[1,1,0]
	s_nop 0
	v_pk_mul_f32 v[136:137], v[136:137], v[140:141]
	s_nop 0
	v_pk_fma_f32 v[132:133], v[132:133], v[136:137], v[132:133]
	s_nop 0
	v_mul_f32_e32 v132, v104, v132
	v_mul_f32_e32 v140, v2, v132
	v_mul_f32_e32 v132, v105, v133
	v_mul_f32_e32 v141, v2, v132
	v_lshlrev_b32_e32 v132, 16, v163
	v_and_b32_e32 v133, 0xffff0000, v163
	v_pk_fma_f32 v[132:133], v[134:135], v[132:133], v[138:139]
	s_nop 0
	v_pk_mul_f32 v[134:135], v[132:133], s[26:27] op_sel_hi:[1,0]
	v_pk_mul_f32 v[132:133], v[132:133], 0.5 op_sel_hi:[1,0]
	v_med3_f32 v134, v134, s71, v224
	v_med3_f32 v135, v135, s71, v224
	v_pk_mul_f32 v[136:137], v[134:135], v[134:135]
	s_nop 0
	v_pk_fma_f32 v[138:139], v[136:137], s[28:29], v[148:149] op_sel_hi:[1,0,0] neg_lo:[1,0,0] neg_hi:[1,0,0]
	s_nop 0
	v_pk_fma_f32 v[138:139], v[136:137], v[138:139], s[34:35] op_sel_hi:[1,1,0]
	s_nop 0
	v_pk_fma_f32 v[138:139], v[136:137], v[138:139], s[36:37] op_sel_hi:[1,1,0]
	s_nop 0
	v_pk_fma_f32 v[138:139], v[136:137], v[138:139], s[38:39] op_sel_hi:[1,1,0]
	s_nop 0
	v_pk_fma_f32 v[138:139], v[136:137], v[138:139], s[40:41] op_sel_hi:[1,1,0]
	s_nop 0
	v_pk_fma_f32 v[138:139], v[136:137], v[138:139], s[42:43] op_sel_hi:[1,1,0]
	s_nop 0
	v_pk_fma_f32 v[136:137], v[136:137], v[138:139], s[44:45] op_sel_hi:[1,1,0]
	s_nop 0
	v_pk_mul_f32 v[134:135], v[134:135], v[136:137]
	s_nop 0
	v_pk_fma_f32 v[132:133], v[132:133], v[134:135], v[132:133]
	s_nop 0
	v_mul_f32_e32 v132, v106, v132
	v_mul_f32_e32 v134, v2, v132
	v_mul_f32_e32 v132, v107, v133
	v_mul_f32_e32 v133, v2, v132
	v_cvt_pk_bf16_f32 v132, v140, v141
	v_cvt_pk_bf16_f32 v133, v134, v133
	global_store_dwordx2 v[160:161], v[132:133], off sc1
	v_add_u32_e32 v132, 4, v150
	v_ashrrev_i32_e32 v133, 31, v132
	v_lshlrev_b64 v[162:163], 1, v[132:133]
	v_lshl_add_u64 v[160:161], s[56:57], 0, v[162:163]
	v_lshlrev_b64 v[132:133], 2, v[132:133]
	v_mad_i64_i32 v[134:135], s[8:9], v210, s67, v[160:161]
	v_lshl_add_u64 v[226:227], s[16:17], 0, v[132:133]
	global_load_dwordx2 v[182:183], v[134:135], off
	v_mad_i64_i32 v[134:135], s[8:9], v151, s70, v[226:227]
	v_add_co_u32_e64 v136, s[8:9], s41, v134
	s_waitcnt vmcnt(0)
; __device__ __forceinline__ unsigned cvt_pk_bf16(float lo, float hi) { unsigned r; asm volatile("v_cvt_pk_bf16_f32 %0, %1, %2" : "=v"(r) : "v"(lo), "v"(hi)); return r; }
;     static __device__ __forceinline__ void finish(const float (&g0)[4], const float (&g1)[4], const float (&g2)[4], const float (&w0)[4], const float (&w1)[4], const float (&w2)[4], const float (&bb)[4],
;                                                   const f32x4 v, float rs, bf16_t* dst) {
;         float h[4];
; #pragma unroll
;         for (int j = 0; j < 4; j += 2) {
;             const f32x2 gc = (f32x2){bb[j] + w0[j] * g2[j] + w1[j] * g1[j] + w2[j] * g0[j], bb[j + 1] + w0[j + 1] * g2[j + 1] + w1[j + 1] * g1[j + 1] + w2[j + 1] * g0[j + 1]};
;             const f32x2 ge = gelu_pk(gc); h[j] = ge.x * v[j] * rs; h[j + 1] = ge.y * v[j + 1] * rs; }
;         u32x2 w; w.x = cvt_pk_bf16(h[0], h[1]); w.y = cvt_pk_bf16(h[2], h[3]);
;         *(u32x2*)dst = w;
;     }
;     __device__ __forceinline__ void operator()(const f32x4 (&acc)[2][2][4][2], const Unit& u, int wr, int wc, int fr, int fq) const {
;     ...
;             float w0[4], w1[4], w2[4], bb[4];
;             ld4f(cw + col, w0); ld4f(cw + 2816 + col, w1); ld4f(cw + 2 * 2816 + col, w2); ld4f(cb + col, bb);
;             {
;                 const int i = fr & 7;
;                 u32x2 gq[4];
; #pragma unroll
;                 for (int m = 0; m < 4; ++m) { const int row = row0 + m * 16; gq[m] = *(const u32x2*)(G + (size_t)row * 2816 + col); }
; #pragma unroll
;                 for (int mh = 0; mh < 4; mh += 2) {
;                 f32x4 c0[4], c1[4];
; #pragma unroll
;                 for (int m = mh; m < mh + 2; ++m) { const int row = row0 + m * 16; const float* cx = ctx + (size_t)((row - 32768) >> 3) * 2 * 2816 + col;
;                     c0[m] = *(const f32x4*)cx; c1[m] = *(const f32x4*)(cx + 2816); }
; #pragma unroll
;                 for (int m = mh; m < mh + 2; ++m) { const int row = row0 + m * 16; const u32x2 cur = gq[m];
;                     const u32x2 q1 = dpp_prev<1>(cur, cur), q2 = dpp_prev<2>(cur, cur);
;                     float g0[4], g1[4], g2[4]; unpk4(cur, g0); unpk4(q1, g1); unpk4(q2, g2);
; #pragma unroll
;                     for (int j = 0; j < 4; ++j) { const float x1 = c1[m][j], x0 = c0[m][j];
;                         if (i < 1) g1[j] = x1;
;                         if (i < 2) g2[j] = (i == 1) ? x1 : x0; }
	v_mov_b32_dpp v169, v182 row_ror:1 row_mask:0xf bank_mask:0xf bound_ctrl:1
	v_addc_co_u32_e64 v137, s[8:9], 0, v135, s[8:9]
	global_load_dwordx4 v[170:173], v[136:137], off offset:3072
	global_load_dwordx4 v[174:177], v[134:135], off
	v_lshl_add_u64 v[134:135], s[12:13], 0, v[132:133]
	global_load_dwordx4 v[140:143], v[134:135], off
	v_lshl_add_u64 v[134:135], s[14:15], 0, v[132:133]
	global_load_dwordx4 v[144:147], v[134:135], off
	v_lshl_add_u64 v[134:135], s[18:19], 0, v[132:133]
	global_load_dwordx4 v[136:139], v[134:135], off
	v_lshl_add_u64 v[132:133], s[20:21], 0, v[132:133]
	global_load_dwordx4 v[132:135], v[132:133], off
	v_mad_i64_i32 v[164:165], s[8:9], v194, s67, v[160:161]
	v_mad_i64_i32 v[178:179], s[8:9], v192, s67, v[160:161]
	v_mad_i64_i32 v[160:161], s[8:9], v190, s67, v[160:161]
	global_load_dwordx2 v[228:229], v[164:165], off
	s_nop 0
	global_load_dwordx2 v[164:165], v[178:179], off
	s_nop 0
	global_load_dwordx2 v[160:161], v[160:161], off
	v_mad_i64_i32 v[178:179], s[8:9], v166, s70, v[226:227]
	v_add_co_u32_e64 v212, s[8:9], s41, v178
	v_mov_b32_dpp v169, v182 row_shr:1 row_mask:0xf bank_mask:0xf
	s_nop 0
	v_addc_co_u32_e64 v213, s[8:9], 0, v179, s[8:9]
	global_load_dwordx4 v[178:181], v[178:179], off
	s_nop 0
	global_load_dwordx4 v[212:215], v[212:213], off offset:3072
	v_mov_b32_dpp v185, v183 row_ror:1 row_mask:0xf bank_mask:0xf bound_ctrl:1
	v_mov_b32_dpp v187, v182 row_ror:2 row_mask:0xf bank_mask:0xf bound_ctrl:1
	v_lshlrev_b32_e32 v191, 16, v169
	v_mov_b32_dpp v185, v183 row_shr:1 row_mask:0xf bank_mask:0xf
	v_mov_b32_dpp v187, v182 row_shr:2 row_mask:0xf bank_mask:0xf
	v_and_b32_e32 v169, 0xffff0000, v169
	v_lshlrev_b32_e32 v193, 16, v185
	v_and_b32_e32 v185, 0xffff0000, v185
	v_lshlrev_b32_e32 v195, 16, v187
	v_and_b32_e32 v187, 0xffff0000, v187
	v_mov_b32_dpp v189, v183 row_ror:2 row_mask:0xf bank_mask:0xf bound_ctrl:1
	s_waitcnt vmcnt(10)
	v_cndmask_b32_e64 v231, v169, v171, s[6:7]
	s_waitcnt vmcnt(9)
	v_cndmask_b32_e32 v169, v174, v170, vcc
	v_cndmask_b32_e32 v174, v175, v171, vcc
	v_cndmask_b32_e64 v230, v191, v170, s[6:7]
	v_cndmask_b32_e64 v233, v185, v173, s[6:7]
	v_cndmask_b32_e64 v232, v193, v172, s[6:7]
	v_cndmask_b32_e32 v170, v176, v172, vcc
	v_cndmask_b32_e32 v171, v177, v173, vcc
	v_cndmask_b32_e64 v173, v187, v174, s[0:1]
	v_cndmask_b32_e64 v172, v195, v169, s[0:1]
	s_waitcnt vmcnt(7)
	v_pk_fma_f32 v[172:173], v[140:141], v[172:173], v[144:145]
	v_lshlrev_b32_e32 v176, 16, v182
	v_and_b32_e32 v177, 0xffff0000, v182
	s_waitcnt vmcnt(6)
	v_pk_fma_f32 v[172:173], v[136:137], v[230:231], v[172:173]
	v_mov_b32_dpp v189, v183 row_shr:2 row_mask:0xf bank_mask:0xf
	s_waitcnt vmcnt(5)
	v_pk_fma_f32 v[172:173], v[132:133], v[176:177], v[172:173]
	v_lshlrev_b32_e32 v211, 16, v189
	v_and_b32_e32 v189, 0xffff0000, v189
	v_pk_mul_f32 v[176:177], v[172:173], s[26:27] op_sel_hi:[1,0]
	v_cndmask_b32_e64 v171, v189, v171, s[0:1]
	v_cndmask_b32_e64 v170, v211, v170, s[0:1]
	v_med3_f32 v176, v176, s71, v224
	v_med3_f32 v177, v177, s71, v224
	v_pk_fma_f32 v[170:171], v[142:143], v[170:171], v[146:147]
	v_pk_mul_f32 v[230:231], v[176:177], v[176:177]
	v_pk_fma_f32 v[170:171], v[138:139], v[232:233], v[170:171]
	v_pk_fma_f32 v[232:233], v[230:231], s[28:29], v[148:149] op_sel_hi:[1,0,0] neg_lo:[1,0,0] neg_hi:[1,0,0]
	v_pk_mul_f32 v[172:173], v[172:173], 0.5 op_sel_hi:[1,0]
	v_pk_fma_f32 v[232:233], v[230:231], v[232:233], s[34:35] op_sel_hi:[1,1,0]
	v_lshl_add_u64 v[174:175], v[152:153], 0, v[162:163]
	v_pk_fma_f32 v[232:233], v[230:231], v[232:233], s[36:37] op_sel_hi:[1,1,0]
	s_nop 0
	v_pk_fma_f32 v[232:233], v[230:231], v[232:233], s[38:39] op_sel_hi:[1,1,0]
	s_nop 0
	v_pk_fma_f32 v[232:233], v[230:231], v[232:233], s[40:41] op_sel_hi:[1,1,0]
	s_nop 0
	v_pk_fma_f32 v[232:233], v[230:231], v[232:233], s[42:43] op_sel_hi:[1,1,0]
	s_nop 0
	v_pk_fma_f32 v[230:231], v[230:231], v[232:233], s[44:45] op_sel_hi:[1,1,0]
	s_nop 0
	v_pk_mul_f32 v[176:177], v[176:177], v[230:231]
	s_nop 0
	v_pk_fma_f32 v[172:173], v[172:173], v[176:177], v[172:173]
	s_nop 0
	v_mul_f32_e32 v169, v124, v172
	v_mul_f32_e32 v172, v125, v173
	v_mul_f32_e32 v185, v188, v172
	v_lshlrev_b32_e32 v172, 16, v183
	v_and_b32_e32 v173, 0xffff0000, v183
	v_pk_fma_f32 v[170:171], v[134:135], v[172:173], v[170:171]
	v_mul_f32_e32 v169, v188, v169
	v_pk_mul_f32 v[172:173], v[170:171], s[26:27] op_sel_hi:[1,0]
	v_pk_mul_f32 v[170:171], v[170:171], 0.5 op_sel_hi:[1,0]
	v_med3_f32 v172, v172, s71, v224
	v_med3_f32 v173, v173, s71, v224
	v_pk_mul_f32 v[176:177], v[172:173], v[172:173]
	s_nop 0
	v_pk_fma_f32 v[182:183], v[176:177], s[28:29], v[148:149] op_sel_hi:[1,0,0] neg_lo:[1,0,0] neg_hi:[1,0,0]
	s_nop 0
	v_pk_fma_f32 v[182:183], v[176:177], v[182:183], s[34:35] op_sel_hi:[1,1,0]
	s_nop 0
	v_pk_fma_f32 v[182:183], v[176:177], v[182:183], s[36:37] op_sel_hi:[1,1,0]
	s_nop 0
	v_pk_fma_f32 v[182:183], v[176:177], v[182:183], s[38:39] op_sel_hi:[1,1,0]
	s_nop 0
	v_pk_fma_f32 v[182:183], v[176:177], v[182:183], s[40:41] op_sel_hi:[1,1,0]
	s_nop 0
	v_pk_fma_f32 v[182:183], v[176:177], v[182:183], s[42:43] op_sel_hi:[1,1,0]
	s_nop 0
	v_pk_fma_f32 v[176:177], v[176:177], v[182:183], s[44:45] op_sel_hi:[1,1,0]
	s_nop 0
	v_pk_mul_f32 v[172:173], v[172:173], v[176:177]
	s_nop 0
	v_pk_fma_f32 v[170:171], v[170:171], v[172:173], v[170:171]
	s_nop 0
	v_mul_f32_e32 v170, v126, v170
	v_mul_f32_e32 v172, v188, v170
	v_mul_f32_e32 v170, v127, v171
	v_mul_f32_e32 v171, v188, v170
	v_cvt_pk_bf16_f32 v170, v169, v185
	v_cvt_pk_bf16_f32 v171, v172, v171
	s_waitcnt vmcnt(4)
; __device__ __forceinline__ unsigned cvt_pk_bf16(float lo, float hi) { unsigned r; asm volatile("v_cvt_pk_bf16_f32 %0, %1, %2" : "=v"(r) : "v"(lo), "v"(hi)); return r; }
;     static __device__ __forceinline__ void finish(const float (&g0)[4], const float (&g1)[4], const float (&g2)[4], const float (&w0)[4], const float (&w1)[4], const float (&w2)[4], const float (&bb)[4],
;                                                   const f32x4 v, float rs, bf16_t* dst) {
;         float h[4];
; #pragma unroll
;         for (int j = 0; j < 4; j += 2) {
;             const f32x2 gc = (f32x2){bb[j] + w0[j] * g2[j] + w1[j] * g1[j] + w2[j] * g0[j], bb[j + 1] + w0[j + 1] * g2[j + 1] + w1[j + 1] * g1[j + 1] + w2[j + 1] * g0[j + 1]};
;             const f32x2 ge = gelu_pk(gc); h[j] = ge.x * v[j] * rs; h[j + 1] = ge.y * v[j + 1] * rs; }
;         u32x2 w; w.x = cvt_pk_bf16(h[0], h[1]); w.y = cvt_pk_bf16(h[2], h[3]);
;         *(u32x2*)dst = w;
;     }
;     __device__ __forceinline__ void operator()(const f32x4 (&acc)[2][2][4][2], const Unit& u, int wr, int wc, int fr, int fq) const {
;     ...
;                 u32x2 gq[4];
; #pragma unroll
;                 for (int m = 0; m < 4; ++m) { const int row = row0 + m * 16; gq[m] = *(const u32x2*)(G + (size_t)row * 2816 + col); }
; #pragma unroll
;                 for (int mh = 0; mh < 4; mh += 2) {
;                 f32x4 c0[4], c1[4];
; #pragma unroll
;                 for (int m = mh; m < mh + 2; ++m) { const int row = row0 + m * 16; const float* cx = ctx + (size_t)((row - 32768) >> 3) * 2 * 2816 + col;
;                     c0[m] = *(const f32x4*)cx; c1[m] = *(const f32x4*)(cx + 2816); }
; #pragma unroll
;                 for (int m = mh; m < mh + 2; ++m) { const int row = row0 + m * 16; const u32x2 cur = gq[m];
;                     const u32x2 q1 = dpp_prev<1>(cur, cur), q2 = dpp_prev<2>(cur, cur);
;                     float g0[4], g1[4], g2[4]; unpk4(cur, g0); unpk4(q1, g1); unpk4(q2, g2);
; #pragma unroll
;                     for (int j = 0; j < 4; ++j) { const float x1 = c1[m][j], x0 = c0[m][j];
;                         if (i < 1) g1[j] = x1;
;                         if (i < 2) g2[j] = (i == 1) ? x1 : x0; }
;                     finish(g0, g1, g2, w0, w1, w2, bb, acc[0][bj][m][hv], rs8[0][m], H + (size_t)row * 2816 + col); }
;                 }
	v_mov_b32_dpp v169, v228 row_ror:1 row_mask:0xf bank_mask:0xf bound_ctrl:1
	global_store_dwordx2 v[174:175], v[170:171], off sc1
	v_mov_b32_dpp v171, v228 row_ror:2 row_mask:0xf bank_mask:0xf bound_ctrl:1
	v_mov_b32_dpp v169, v228 row_shr:1 row_mask:0xf bank_mask:0xf
	v_mov_b32_dpp v170, v229 row_ror:1 row_mask:0xf bank_mask:0xf bound_ctrl:1
	v_mov_b32_dpp v171, v228 row_shr:2 row_mask:0xf bank_mask:0xf
	v_lshlrev_b32_e32 v173, 16, v169
	v_and_b32_e32 v169, 0xffff0000, v169
	v_mov_b32_dpp v170, v229 row_shr:1 row_mask:0xf bank_mask:0xf
	v_mov_b32_dpp v172, v229 row_ror:2 row_mask:0xf bank_mask:0xf bound_ctrl:1
	v_lshlrev_b32_e32 v176, 16, v171
	v_and_b32_e32 v177, 0xffff0000, v171
	s_waitcnt vmcnt(1)
	v_cndmask_b32_e64 v171, v169, v213, s[6:7]
	v_cndmask_b32_e32 v169, v178, v212, vcc
	v_cndmask_b32_e32 v178, v179, v213, vcc
	v_mov_b32_dpp v172, v229 row_shr:2 row_mask:0xf bank_mask:0xf
	v_lshlrev_b32_e32 v174, 16, v170
	v_and_b32_e32 v175, 0xffff0000, v170
	v_cndmask_b32_e64 v177, v177, v178, s[0:1]
	v_cndmask_b32_e64 v176, v176, v169, s[0:1]
	v_lshlrev_b32_e32 v182, 16, v172
	v_and_b32_e32 v183, 0xffff0000, v172
	v_cndmask_b32_e64 v170, v173, v212, s[6:7]
	v_cndmask_b32_e64 v173, v175, v215, s[6:7]
	v_cndmask_b32_e64 v172, v174, v214, s[6:7]
	v_cndmask_b32_e32 v174, v180, v214, vcc
	v_cndmask_b32_e32 v175, v181, v215, vcc
	v_pk_fma_f32 v[176:177], v[140:141], v[176:177], v[144:145]
	v_cndmask_b32_e64 v175, v183, v175, s[0:1]
	v_cndmask_b32_e64 v174, v182, v174, s[0:1]
	v_lshlrev_b32_e32 v180, 16, v228
	v_and_b32_e32 v181, 0xffff0000, v228
	v_pk_fma_f32 v[170:171], v[136:137], v[170:171], v[176:177]
	v_pk_fma_f32 v[174:175], v[142:143], v[174:175], v[146:147]
	v_pk_fma_f32 v[170:171], v[132:133], v[180:181], v[170:171]
	v_pk_fma_f32 v[172:173], v[138:139], v[172:173], v[174:175]
	v_pk_mul_f32 v[174:175], v[170:171], s[26:27] op_sel_hi:[1,0]
	v_pk_mul_f32 v[170:171], v[170:171], 0.5 op_sel_hi:[1,0]
	v_med3_f32 v174, v174, s71, v224
	v_med3_f32 v175, v175, s71, v224
	v_pk_mul_f32 v[176:177], v[174:175], v[174:175]
	v_lshl_add_u64 v[178:179], v[154:155], 0, v[162:163]
	v_pk_fma_f32 v[180:181], v[176:177], s[28:29], v[148:149] op_sel_hi:[1,0,0] neg_lo:[1,0,0] neg_hi:[1,0,0]
	v_mov_b32_dpp v185, v165 row_ror:2 row_mask:0xf bank_mask:0xf bound_ctrl:1
	v_pk_fma_f32 v[180:181], v[176:177], v[180:181], s[34:35] op_sel_hi:[1,1,0]
	s_nop 0
	v_pk_fma_f32 v[180:181], v[176:177], v[180:181], s[36:37] op_sel_hi:[1,1,0]
	v_mov_b32_dpp v185, v165 row_shr:2 row_mask:0xf bank_mask:0xf
	v_pk_fma_f32 v[180:181], v[176:177], v[180:181], s[38:39] op_sel_hi:[1,1,0]
	v_lshlrev_b32_e32 v211, 16, v185
	v_pk_fma_f32 v[180:181], v[176:177], v[180:181], s[40:41] op_sel_hi:[1,1,0]
	v_and_b32_e32 v185, 0xffff0000, v185
	v_pk_fma_f32 v[180:181], v[176:177], v[180:181], s[42:43] op_sel_hi:[1,1,0]
	s_nop 0
	v_pk_fma_f32 v[176:177], v[176:177], v[180:181], s[44:45] op_sel_hi:[1,1,0]
	s_nop 0
	v_pk_mul_f32 v[174:175], v[174:175], v[176:177]
	s_nop 0
	v_pk_fma_f32 v[170:171], v[170:171], v[174:175], v[170:171]
	s_nop 0
	v_mul_f32_e32 v169, v116, v170
	v_mul_f32_e32 v170, v117, v171
	v_mul_f32_e32 v180, v186, v170
	v_lshlrev_b32_e32 v170, 16, v229
	v_and_b32_e32 v171, 0xffff0000, v229
	v_pk_fma_f32 v[170:171], v[134:135], v[170:171], v[172:173]
	v_mul_f32_e32 v169, v186, v169
	v_pk_mul_f32 v[172:173], v[170:171], s[26:27] op_sel_hi:[1,0]
	v_pk_mul_f32 v[170:171], v[170:171], 0.5 op_sel_hi:[1,0]
	v_med3_f32 v172, v172, s71, v224
	v_med3_f32 v173, v173, s71, v224
	v_pk_mul_f32 v[174:175], v[172:173], v[172:173]
	s_nop 0
	v_pk_fma_f32 v[176:177], v[174:175], s[28:29], v[148:149] op_sel_hi:[1,0,0] neg_lo:[1,0,0] neg_hi:[1,0,0]
	s_nop 0
	v_pk_fma_f32 v[176:177], v[174:175], v[176:177], s[34:35] op_sel_hi:[1,1,0]
	s_nop 0
	v_pk_fma_f32 v[176:177], v[174:175], v[176:177], s[36:37] op_sel_hi:[1,1,0]
	s_nop 0
	v_pk_fma_f32 v[176:177], v[174:175], v[176:177], s[38:39] op_sel_hi:[1,1,0]
	s_nop 0
	v_pk_fma_f32 v[176:177], v[174:175], v[176:177], s[40:41] op_sel_hi:[1,1,0]
	s_nop 0
	v_pk_fma_f32 v[176:177], v[174:175], v[176:177], s[42:43] op_sel_hi:[1,1,0]
	s_nop 0
	v_pk_fma_f32 v[174:175], v[174:175], v[176:177], s[44:45] op_sel_hi:[1,1,0]
	s_nop 0
	v_pk_mul_f32 v[172:173], v[172:173], v[174:175]
	v_mad_i64_i32 v[174:175], s[8:9], v167, s70, v[226:227]
	v_pk_fma_f32 v[170:171], v[170:171], v[172:173], v[170:171]
	s_nop 0
	v_mul_f32_e32 v170, v118, v170
	v_mul_f32_e32 v172, v186, v170
	v_mul_f32_e32 v170, v119, v171
	v_mul_f32_e32 v171, v186, v170
	v_cvt_pk_bf16_f32 v170, v169, v180
	v_cvt_pk_bf16_f32 v171, v172, v171
	global_store_dwordx2 v[178:179], v[170:171], off sc1
	v_add_co_u32_e64 v170, s[8:9], s41, v174
	v_mov_b32_dpp v169, v164 row_ror:1 row_mask:0xf bank_mask:0xf bound_ctrl:1
	s_nop 0
	v_addc_co_u32_e64 v171, s[8:9], 0, v175, s[8:9]
	global_load_dwordx4 v[170:173], v[170:171], off offset:3072
	s_nop 0
	global_load_dwordx4 v[174:177], v[174:175], off
	v_mad_i64_i32 v[178:179], s[8:9], v168, s70, v[226:227]
	v_add_co_u32_e64 v182, s[8:9], s41, v178
	v_mov_b32_dpp v169, v164 row_shr:1 row_mask:0xf bank_mask:0xf
	s_nop 0
	v_addc_co_u32_e64 v183, s[8:9], 0, v179, s[8:9]
	global_load_dwordx4 v[178:181], v[178:179], off
	s_nop 0
	global_load_dwordx4 v[212:215], v[182:183], off offset:3072
	v_mov_b32_dpp v182, v165 row_ror:1 row_mask:0xf bank_mask:0xf bound_ctrl:1
	v_mov_b32_dpp v183, v164 row_ror:2 row_mask:0xf bank_mask:0xf bound_ctrl:1
	v_lshlrev_b32_e32 v187, 16, v169
	v_mov_b32_dpp v182, v165 row_shr:1 row_mask:0xf bank_mask:0xf
	v_mov_b32_dpp v183, v164 row_shr:2 row_mask:0xf bank_mask:0xf
	v_and_b32_e32 v169, 0xffff0000, v169
	v_lshlrev_b32_e32 v189, 16, v182
	v_and_b32_e32 v191, 0xffff0000, v182
	v_lshlrev_b32_e32 v193, 16, v183
	v_and_b32_e32 v195, 0xffff0000, v183
	s_waitcnt vmcnt(3)
; __device__ __forceinline__ unsigned cvt_pk_bf16(float lo, float hi) { unsigned r; asm volatile("v_cvt_pk_bf16_f32 %0, %1, %2" : "=v"(r) : "v"(lo), "v"(hi)); return r; }
;     static __device__ __forceinline__ void finish(const float (&g0)[4], const float (&g1)[4], const float (&g2)[4], const float (&w0)[4], const float (&w1)[4], const float (&w2)[4], const float (&bb)[4],
;                                                   const f32x4 v, float rs, bf16_t* dst) {
;         float h[4];
; #pragma unroll
;         for (int j = 0; j < 4; j += 2) {
;             const f32x2 gc = (f32x2){bb[j] + w0[j] * g2[j] + w1[j] * g1[j] + w2[j] * g0[j], bb[j + 1] + w0[j + 1] * g2[j + 1] + w1[j + 1] * g1[j + 1] + w2[j + 1] * g0[j + 1]};
;             const f32x2 ge = gelu_pk(gc); h[j] = ge.x * v[j] * rs; h[j + 1] = ge.y * v[j + 1] * rs; }
;         u32x2 w; w.x = cvt_pk_bf16(h[0], h[1]); w.y = cvt_pk_bf16(h[2], h[3]);
;         *(u32x2*)dst = w;
;     }
;     __device__ __forceinline__ void operator()(const f32x4 (&acc)[2][2][4][2], const Unit& u, int wr, int wc, int fr, int fq) const {
;     ...
;                 u32x2 gq[4];
; #pragma unroll
;                 for (int m = 0; m < 4; ++m) { const int row = row0 + m * 16; gq[m] = *(const u32x2*)(G + (size_t)row * 2816 + col); }
; #pragma unroll
;                 for (int mh = 0; mh < 4; mh += 2) {
;                 f32x4 c0[4], c1[4];
; #pragma unroll
;                 for (int m = mh; m < mh + 2; ++m) { const int row = row0 + m * 16; const float* cx = ctx + (size_t)((row - 32768) >> 3) * 2 * 2816 + col;
;                     c0[m] = *(const f32x4*)cx; c1[m] = *(const f32x4*)(cx + 2816); }
; #pragma unroll
;                 for (int m = mh; m < mh + 2; ++m) { const int row = row0 + m * 16; const u32x2 cur = gq[m];
;                     const u32x2 q1 = dpp_prev<1>(cur, cur), q2 = dpp_prev<2>(cur, cur);
;                     float g0[4], g1[4], g2[4]; unpk4(cur, g0); unpk4(q1, g1); unpk4(q2, g2);
; #pragma unroll
;                     for (int j = 0; j < 4; ++j) { const float x1 = c1[m][j], x0 = c0[m][j];
;                         if (i < 1) g1[j] = x1;
;                         if (i < 2) g2[j] = (i == 1) ? x1 : x0; }
;                     finish(g0, g1, g2, w0, w1, w2, bb, acc[0][bj][m][hv], rs8[0][m], H + (size_t)row * 2816 + col); }
;                 }
	v_cndmask_b32_e64 v183, v169, v171, s[6:7]
	s_waitcnt vmcnt(2)
	v_cndmask_b32_e32 v169, v174, v170, vcc
	v_cndmask_b32_e32 v174, v175, v171, vcc
	v_cndmask_b32_e64 v182, v187, v170, s[6:7]
	v_cndmask_b32_e64 v227, v191, v173, s[6:7]
	v_cndmask_b32_e64 v226, v189, v172, s[6:7]
	v_cndmask_b32_e32 v170, v176, v172, vcc
	v_cndmask_b32_e32 v171, v177, v173, vcc
	v_cndmask_b32_e64 v173, v195, v174, s[0:1]
	v_cndmask_b32_e64 v172, v193, v169, s[0:1]
	v_pk_fma_f32 v[172:173], v[140:141], v[172:173], v[144:145]
	v_lshlrev_b32_e32 v176, 16, v164
	v_and_b32_e32 v177, 0xffff0000, v164
	v_pk_fma_f32 v[172:173], v[136:137], v[182:183], v[172:173]
	v_cndmask_b32_e64 v171, v185, v171, s[0:1]
	v_pk_fma_f32 v[172:173], v[132:133], v[176:177], v[172:173]
	v_cndmask_b32_e64 v170, v211, v170, s[0:1]
	v_pk_mul_f32 v[176:177], v[172:173], s[26:27] op_sel_hi:[1,0]
	v_pk_fma_f32 v[170:171], v[142:143], v[170:171], v[146:147]
	v_med3_f32 v176, v176, s71, v224
	v_med3_f32 v177, v177, s71, v224
	v_pk_mul_f32 v[182:183], v[176:177], v[176:177]
	v_pk_fma_f32 v[170:171], v[138:139], v[226:227], v[170:171]
	v_pk_fma_f32 v[226:227], v[182:183], s[28:29], v[148:149] op_sel_hi:[1,0,0] neg_lo:[1,0,0] neg_hi:[1,0,0]
	v_pk_mul_f32 v[172:173], v[172:173], 0.5 op_sel_hi:[1,0]
	v_pk_fma_f32 v[226:227], v[182:183], v[226:227], s[34:35] op_sel_hi:[1,1,0]
	v_lshl_add_u64 v[174:175], v[156:157], 0, v[162:163]
	v_pk_fma_f32 v[226:227], v[182:183], v[226:227], s[36:37] op_sel_hi:[1,1,0]
	v_lshl_add_u64 v[162:163], v[158:159], 0, v[162:163]
	v_pk_fma_f32 v[226:227], v[182:183], v[226:227], s[38:39] op_sel_hi:[1,1,0]
	s_nop 0
	v_pk_fma_f32 v[226:227], v[182:183], v[226:227], s[40:41] op_sel_hi:[1,1,0]
	s_nop 0
	v_pk_fma_f32 v[226:227], v[182:183], v[226:227], s[42:43] op_sel_hi:[1,1,0]
	s_nop 0
	v_pk_fma_f32 v[182:183], v[182:183], v[226:227], s[44:45] op_sel_hi:[1,1,0]
	s_nop 0
	v_pk_mul_f32 v[176:177], v[176:177], v[182:183]
	s_nop 0
	v_pk_fma_f32 v[172:173], v[172:173], v[176:177], v[172:173]
	s_nop 0
	v_mul_f32_e32 v164, v108, v172
	v_mul_f32_e32 v169, v184, v164
	v_mul_f32_e32 v164, v109, v173
	v_mul_f32_e32 v182, v184, v164
	v_lshlrev_b32_e32 v164, 16, v165
	v_and_b32_e32 v165, 0xffff0000, v165
	v_pk_fma_f32 v[164:165], v[134:135], v[164:165], v[170:171]
	s_nop 0
	v_pk_mul_f32 v[170:171], v[164:165], s[26:27] op_sel_hi:[1,0]
	v_pk_mul_f32 v[164:165], v[164:165], 0.5 op_sel_hi:[1,0]
	v_med3_f32 v170, v170, s71, v224
	v_med3_f32 v171, v171, s71, v224
	v_pk_mul_f32 v[172:173], v[170:171], v[170:171]
	s_nop 0
	v_pk_fma_f32 v[176:177], v[172:173], s[28:29], v[148:149] op_sel_hi:[1,0,0] neg_lo:[1,0,0] neg_hi:[1,0,0]
	s_nop 0
	v_pk_fma_f32 v[176:177], v[172:173], v[176:177], s[34:35] op_sel_hi:[1,1,0]
	s_nop 0
	v_pk_fma_f32 v[176:177], v[172:173], v[176:177], s[36:37] op_sel_hi:[1,1,0]
	s_nop 0
	v_pk_fma_f32 v[176:177], v[172:173], v[176:177], s[38:39] op_sel_hi:[1,1,0]
	s_nop 0
	v_pk_fma_f32 v[176:177], v[172:173], v[176:177], s[40:41] op_sel_hi:[1,1,0]
	s_nop 0
	v_pk_fma_f32 v[176:177], v[172:173], v[176:177], s[42:43] op_sel_hi:[1,1,0]
	s_nop 0
	v_pk_fma_f32 v[172:173], v[172:173], v[176:177], s[44:45] op_sel_hi:[1,1,0]
	s_waitcnt vmcnt(0)
	v_cndmask_b32_e32 v177, v178, v212, vcc
	v_pk_mul_f32 v[170:171], v[170:171], v[172:173]
	v_cndmask_b32_e32 v178, v179, v213, vcc
	v_pk_fma_f32 v[164:165], v[164:165], v[170:171], v[164:165]
	s_nop 0
	v_mul_f32_e32 v164, v110, v164
	v_mul_f32_e32 v170, v184, v164
	v_mul_f32_e32 v164, v111, v165
	v_mul_f32_e32 v165, v184, v164
	v_cvt_pk_bf16_f32 v164, v169, v182
	v_cvt_pk_bf16_f32 v165, v170, v165
	global_store_dwordx2 v[174:175], v[164:165], off sc1
	v_mov_b32_dpp v169, v160 row_ror:2 row_mask:0xf bank_mask:0xf bound_ctrl:1
	v_mov_b32_dpp v165, v161 row_ror:1 row_mask:0xf bank_mask:0xf bound_ctrl:1
	v_mov_b32_dpp v170, v161 row_ror:2 row_mask:0xf bank_mask:0xf bound_ctrl:1
	v_mov_b32_dpp v164, v160 row_ror:1 row_mask:0xf bank_mask:0xf bound_ctrl:1
	v_mov_b32_dpp v165, v161 row_shr:1 row_mask:0xf bank_mask:0xf
	v_mov_b32_dpp v169, v160 row_shr:2 row_mask:0xf bank_mask:0xf
	v_mov_b32_dpp v170, v161 row_shr:2 row_mask:0xf bank_mask:0xf
	v_lshlrev_b32_e32 v172, 16, v165
	v_mov_b32_dpp v164, v160 row_shr:1 row_mask:0xf bank_mask:0xf
	v_lshlrev_b32_e32 v174, 16, v169
	v_and_b32_e32 v169, 0xffff0000, v169
	v_lshlrev_b32_e32 v175, 16, v170
	v_and_b32_e32 v176, 0xffff0000, v170
	v_cndmask_b32_e64 v170, v172, v214, s[6:7]
	v_cndmask_b32_e32 v172, v180, v214, vcc
	v_lshlrev_b32_e32 v171, 16, v164
	v_and_b32_e32 v164, 0xffff0000, v164
	v_and_b32_e32 v173, 0xffff0000, v165
	v_cndmask_b32_e64 v172, v175, v172, s[0:1]
	v_cndmask_b32_e64 v175, v169, v178, s[0:1]
	v_cndmask_b32_e64 v174, v174, v177, s[0:1]
	v_cndmask_b32_e64 v165, v164, v213, s[6:7]
	v_cndmask_b32_e64 v164, v171, v212, s[6:7]
	v_cndmask_b32_e64 v171, v173, v215, s[6:7]
	v_cndmask_b32_e32 v173, v181, v215, vcc
	v_pk_fma_f32 v[140:141], v[140:141], v[174:175], v[144:145]
	v_cndmask_b32_e64 v173, v176, v173, s[0:1]
	v_lshlrev_b32_e32 v176, 16, v160
	v_and_b32_e32 v177, 0xffff0000, v160
	v_pk_fma_f32 v[136:137], v[136:137], v[164:165], v[140:141]
	v_pk_fma_f32 v[142:143], v[142:143], v[172:173], v[146:147]
	v_pk_fma_f32 v[132:133], v[132:133], v[176:177], v[136:137]
	v_pk_fma_f32 v[138:139], v[138:139], v[170:171], v[142:143]
	v_pk_mul_f32 v[136:137], v[132:133], s[26:27] op_sel_hi:[1,0]
	v_pk_mul_f32 v[132:133], v[132:133], 0.5 op_sel_hi:[1,0]
	v_med3_f32 v136, v136, s71, v224
	v_med3_f32 v137, v137, s71, v224
	v_pk_mul_f32 v[140:141], v[136:137], v[136:137]
	s_nop 0
	v_pk_fma_f32 v[142:143], v[140:141], s[28:29], v[148:149] op_sel_hi:[1,0,0] neg_lo:[1,0,0] neg_hi:[1,0,0]
	s_nop 0
; __device__ __forceinline__ unsigned cvt_pk_bf16(float lo, float hi) { unsigned r; asm volatile("v_cvt_pk_bf16_f32 %0, %1, %2" : "=v"(r) : "v"(lo), "v"(hi)); return r; }
;     static __device__ __forceinline__ void finish(const float (&g0)[4], const float (&g1)[4], const float (&g2)[4], const float (&w0)[4], const float (&w1)[4], const float (&w2)[4], const float (&bb)[4],
;                                                   const f32x4 v, float rs, bf16_t* dst) {
;         float h[4];
; #pragma unroll
;         for (int j = 0; j < 4; j += 2) {
;             const f32x2 gc = (f32x2){bb[j] + w0[j] * g2[j] + w1[j] * g1[j] + w2[j] * g0[j], bb[j + 1] + w0[j + 1] * g2[j + 1] + w1[j + 1] * g1[j + 1] + w2[j + 1] * g0[j + 1]};
;             const f32x2 ge = gelu_pk(gc); h[j] = ge.x * v[j] * rs; h[j + 1] = ge.y * v[j + 1] * rs; }
;         u32x2 w; w.x = cvt_pk_bf16(h[0], h[1]); w.y = cvt_pk_bf16(h[2], h[3]);
;         *(u32x2*)dst = w;
;     }
;     __device__ __forceinline__ void operator()(const f32x4 (&acc)[2][2][4][2], const Unit& u, int wr, int wc, int fr, int fq) const {
;     ...
;           for (int hv = 0; hv < 2; ++hv) {
;             const int col = u.pn * BM + bj * HALF + wc * 32 + 8 * fq + 4 * hv;
;             float w0[4], w1[4], w2[4], bb[4];
;             ld4f(cw + col, w0); ld4f(cw + 2816 + col, w1); ld4f(cw + 2 * 2816 + col, w2); ld4f(cb + col, bb);
;             {
;                 const int i = fr & 7;
;                 u32x2 gq[4];
; #pragma unroll
;                 for (int m = 0; m < 4; ++m) { const int row = row0 + m * 16; gq[m] = *(const u32x2*)(G + (size_t)row * 2816 + col); }
; #pragma unroll
;                 for (int mh = 0; mh < 4; mh += 2) {
;                 f32x4 c0[4], c1[4];
; #pragma unroll
;                 for (int m = mh; m < mh + 2; ++m) { const int row = row0 + m * 16; const float* cx = ctx + (size_t)((row - 32768) >> 3) * 2 * 2816 + col;
;                     c0[m] = *(const f32x4*)cx; c1[m] = *(const f32x4*)(cx + 2816); }
	v_pk_fma_f32 v[142:143], v[140:141], v[142:143], s[34:35] op_sel_hi:[1,1,0]
	s_nop 0
	v_pk_fma_f32 v[142:143], v[140:141], v[142:143], s[36:37] op_sel_hi:[1,1,0]
	s_nop 0
	v_pk_fma_f32 v[142:143], v[140:141], v[142:143], s[38:39] op_sel_hi:[1,1,0]
	s_nop 0
	v_pk_fma_f32 v[142:143], v[140:141], v[142:143], s[40:41] op_sel_hi:[1,1,0]
	s_nop 0
	v_pk_fma_f32 v[142:143], v[140:141], v[142:143], s[42:43] op_sel_hi:[1,1,0]
	s_nop 0
	v_pk_fma_f32 v[140:141], v[140:141], v[142:143], s[44:45] op_sel_hi:[1,1,0]
	s_nop 0
	v_pk_mul_f32 v[136:137], v[136:137], v[140:141]
	s_nop 0
	v_pk_fma_f32 v[132:133], v[132:133], v[136:137], v[132:133]
	s_nop 0
	v_mul_f32_e32 v132, v100, v132
	v_mul_f32_e32 v140, v2, v132
	v_mul_f32_e32 v132, v101, v133
	v_mul_f32_e32 v141, v2, v132
	v_lshlrev_b32_e32 v132, 16, v161
	v_and_b32_e32 v133, 0xffff0000, v161
	v_pk_fma_f32 v[132:133], v[134:135], v[132:133], v[138:139]
	s_nop 0
	v_pk_mul_f32 v[134:135], v[132:133], s[26:27] op_sel_hi:[1,0]
	v_pk_mul_f32 v[132:133], v[132:133], 0.5 op_sel_hi:[1,0]
	v_med3_f32 v134, v134, s71, v224
	v_med3_f32 v135, v135, s71, v224
	v_pk_mul_f32 v[136:137], v[134:135], v[134:135]
	s_nop 0
	v_pk_fma_f32 v[138:139], v[136:137], s[28:29], v[148:149] op_sel_hi:[1,0,0] neg_lo:[1,0,0] neg_hi:[1,0,0]
	s_nop 0
	v_pk_fma_f32 v[138:139], v[136:137], v[138:139], s[34:35] op_sel_hi:[1,1,0]
	s_nop 0
	v_pk_fma_f32 v[138:139], v[136:137], v[138:139], s[36:37] op_sel_hi:[1,1,0]
	s_nop 0
	v_pk_fma_f32 v[138:139], v[136:137], v[138:139], s[38:39] op_sel_hi:[1,1,0]
	s_nop 0
	v_pk_fma_f32 v[138:139], v[136:137], v[138:139], s[40:41] op_sel_hi:[1,1,0]
	s_nop 0
	v_pk_fma_f32 v[138:139], v[136:137], v[138:139], s[42:43] op_sel_hi:[1,1,0]
	s_nop 0
	v_pk_fma_f32 v[136:137], v[136:137], v[138:139], s[44:45] op_sel_hi:[1,1,0]
	s_nop 0
	v_pk_mul_f32 v[134:135], v[134:135], v[136:137]
	s_nop 0
	v_pk_fma_f32 v[132:133], v[132:133], v[134:135], v[132:133]
	s_nop 0
	v_mul_f32_e32 v132, v102, v132
	v_mul_f32_e32 v134, v2, v132
	v_mul_f32_e32 v132, v103, v133
	v_mul_f32_e32 v133, v2, v132
	v_cvt_pk_bf16_f32 v132, v140, v141
	v_cvt_pk_bf16_f32 v133, v134, v133
	global_store_dwordx2 v[162:163], v[132:133], off sc1
	v_add_u32_e32 v132, 0x80, v150
	v_ashrrev_i32_e32 v133, 31, v132
	v_lshlrev_b64 v[162:163], 1, v[132:133]
	v_lshl_add_u64 v[160:161], s[56:57], 0, v[162:163]
	v_lshlrev_b64 v[132:133], 2, v[132:133]
	v_mad_i64_i32 v[134:135], s[8:9], v210, s67, v[160:161]
	v_lshl_add_u64 v[226:227], s[16:17], 0, v[132:133]
	global_load_dwordx2 v[182:183], v[134:135], off
	v_mad_i64_i32 v[134:135], s[8:9], v151, s70, v[226:227]
	v_add_co_u32_e64 v136, s[8:9], s41, v134
	s_waitcnt vmcnt(0)
	v_mov_b32_dpp v169, v182 row_ror:1 row_mask:0xf bank_mask:0xf bound_ctrl:1
	v_addc_co_u32_e64 v137, s[8:9], 0, v135, s[8:9]
	global_load_dwordx4 v[170:173], v[136:137], off offset:3072
	global_load_dwordx4 v[174:177], v[134:135], off
	v_lshl_add_u64 v[134:135], s[12:13], 0, v[132:133]
	global_load_dwordx4 v[140:143], v[134:135], off
	v_lshl_add_u64 v[134:135], s[14:15], 0, v[132:133]
	global_load_dwordx4 v[144:147], v[134:135], off
	v_lshl_add_u64 v[134:135], s[18:19], 0, v[132:133]
	global_load_dwordx4 v[136:139], v[134:135], off
	v_lshl_add_u64 v[132:133], s[20:21], 0, v[132:133]
	global_load_dwordx4 v[132:135], v[132:133], off
	v_mad_i64_i32 v[164:165], s[8:9], v194, s67, v[160:161]
	v_mad_i64_i32 v[178:179], s[8:9], v192, s67, v[160:161]
	v_mad_i64_i32 v[160:161], s[8:9], v190, s67, v[160:161]
	global_load_dwordx2 v[228:229], v[164:165], off
	s_nop 0
	global_load_dwordx2 v[164:165], v[178:179], off
	s_nop 0
	global_load_dwordx2 v[160:161], v[160:161], off
	v_mad_i64_i32 v[178:179], s[8:9], v166, s70, v[226:227]
	v_add_co_u32_e64 v212, s[8:9], s41, v178
	v_mov_b32_dpp v169, v182 row_shr:1 row_mask:0xf bank_mask:0xf
	s_nop 0
	v_addc_co_u32_e64 v213, s[8:9], 0, v179, s[8:9]
	global_load_dwordx4 v[178:181], v[178:179], off
	s_nop 0
	global_load_dwordx4 v[212:215], v[212:213], off offset:3072
	v_mov_b32_dpp v185, v183 row_ror:1 row_mask:0xf bank_mask:0xf bound_ctrl:1
	v_mov_b32_dpp v187, v182 row_ror:2 row_mask:0xf bank_mask:0xf bound_ctrl:1
	v_lshlrev_b32_e32 v191, 16, v169
	v_mov_b32_dpp v185, v183 row_shr:1 row_mask:0xf bank_mask:0xf
	v_mov_b32_dpp v187, v182 row_shr:2 row_mask:0xf bank_mask:0xf
	v_and_b32_e32 v169, 0xffff0000, v169
	v_lshlrev_b32_e32 v193, 16, v185
	v_and_b32_e32 v185, 0xffff0000, v185
	v_lshlrev_b32_e32 v195, 16, v187
	v_and_b32_e32 v187, 0xffff0000, v187
	v_mov_b32_dpp v189, v183 row_ror:2 row_mask:0xf bank_mask:0xf bound_ctrl:1
	s_waitcnt vmcnt(10)
	v_cndmask_b32_e64 v231, v169, v171, s[6:7]
	s_waitcnt vmcnt(9)
	v_cndmask_b32_e32 v169, v174, v170, vcc
	v_cndmask_b32_e32 v174, v175, v171, vcc
	v_cndmask_b32_e64 v230, v191, v170, s[6:7]
	v_cndmask_b32_e64 v233, v185, v173, s[6:7]
	v_cndmask_b32_e64 v232, v193, v172, s[6:7]
	v_cndmask_b32_e32 v170, v176, v172, vcc
	v_cndmask_b32_e32 v171, v177, v173, vcc
	v_cndmask_b32_e64 v173, v187, v174, s[0:1]
	v_cndmask_b32_e64 v172, v195, v169, s[0:1]
	s_waitcnt vmcnt(7)
	v_pk_fma_f32 v[172:173], v[140:141], v[172:173], v[144:145]
	v_lshlrev_b32_e32 v176, 16, v182
	v_and_b32_e32 v177, 0xffff0000, v182
	s_waitcnt vmcnt(6)
	v_pk_fma_f32 v[172:173], v[136:137], v[230:231], v[172:173]
	v_mov_b32_dpp v189, v183 row_shr:2 row_mask:0xf bank_mask:0xf
	s_waitcnt vmcnt(5)
; __device__ __forceinline__ unsigned cvt_pk_bf16(float lo, float hi) { unsigned r; asm volatile("v_cvt_pk_bf16_f32 %0, %1, %2" : "=v"(r) : "v"(lo), "v"(hi)); return r; }
;     static __device__ __forceinline__ void unpk4(const u32x2 w, float (&o)[4]) { o[0] = bf_lo(w.x); o[1] = bf_hi(w.x); o[2] = bf_lo(w.y); o[3] = bf_hi(w.y); }
;     template <int N> static __device__ __forceinline__ u32x2 dpp_prev(const u32x2 pv, const u32x2 cur) { u32x2 r; r.x = dpp_prev1<N>(pv.x, cur.x); r.y = dpp_prev1<N>(pv.y, cur.y); return r; }
;     static __device__ __forceinline__ void finish(const float (&g0)[4], const float (&g1)[4], const float (&g2)[4], const float (&w0)[4], const float (&w1)[4], const float (&w2)[4], const float (&bb)[4],
;                                                   const f32x4 v, float rs, bf16_t* dst) {
;         float h[4];
; #pragma unroll
;         for (int j = 0; j < 4; j += 2) {
;             const f32x2 gc = (f32x2){bb[j] + w0[j] * g2[j] + w1[j] * g1[j] + w2[j] * g0[j], bb[j + 1] + w0[j + 1] * g2[j + 1] + w1[j + 1] * g1[j + 1] + w2[j + 1] * g0[j + 1]};
;             const f32x2 ge = gelu_pk(gc); h[j] = ge.x * v[j] * rs; h[j + 1] = ge.y * v[j + 1] * rs; }
;         u32x2 w; w.x = cvt_pk_bf16(h[0], h[1]); w.y = cvt_pk_bf16(h[2], h[3]);
;         *(u32x2*)dst = w;
;     }
;     __device__ __forceinline__ void operator()(const f32x4 (&acc)[2][2][4][2], const Unit& u, int wr, int wc, int fr, int fq) const {
;     ...
;                 for (int m = mh; m < mh + 2; ++m) { const int row = row0 + m * 16; const u32x2 cur = gq[m];
;                     const u32x2 q1 = dpp_prev<1>(cur, cur), q2 = dpp_prev<2>(cur, cur);
;                     float g0[4], g1[4], g2[4]; unpk4(cur, g0); unpk4(q1, g1); unpk4(q2, g2);
; #pragma unroll
;                     for (int j = 0; j < 4; ++j) { const float x1 = c1[m][j], x0 = c0[m][j];
;                         if (i < 1) g1[j] = x1;
;                         if (i < 2) g2[j] = (i == 1) ? x1 : x0; }
;                     finish(g0, g1, g2, w0, w1, w2, bb, acc[0][bj][m][hv], rs8[0][m], H + (size_t)row * 2816 + col); }
	v_pk_fma_f32 v[172:173], v[132:133], v[176:177], v[172:173]
	v_lshlrev_b32_e32 v211, 16, v189
	v_and_b32_e32 v189, 0xffff0000, v189
	v_pk_mul_f32 v[176:177], v[172:173], s[26:27] op_sel_hi:[1,0]
	v_cndmask_b32_e64 v171, v189, v171, s[0:1]
	v_cndmask_b32_e64 v170, v211, v170, s[0:1]
	v_med3_f32 v176, v176, s71, v224
	v_med3_f32 v177, v177, s71, v224
	v_pk_fma_f32 v[170:171], v[142:143], v[170:171], v[146:147]
	v_pk_mul_f32 v[230:231], v[176:177], v[176:177]
	v_pk_fma_f32 v[170:171], v[138:139], v[232:233], v[170:171]
	v_pk_fma_f32 v[232:233], v[230:231], s[28:29], v[148:149] op_sel_hi:[1,0,0] neg_lo:[1,0,0] neg_hi:[1,0,0]
	v_pk_mul_f32 v[172:173], v[172:173], 0.5 op_sel_hi:[1,0]
	v_pk_fma_f32 v[232:233], v[230:231], v[232:233], s[34:35] op_sel_hi:[1,1,0]
	v_lshl_add_u64 v[174:175], v[152:153], 0, v[162:163]
	v_pk_fma_f32 v[232:233], v[230:231], v[232:233], s[36:37] op_sel_hi:[1,1,0]
	s_nop 0
	v_pk_fma_f32 v[232:233], v[230:231], v[232:233], s[38:39] op_sel_hi:[1,1,0]
	s_nop 0
	v_pk_fma_f32 v[232:233], v[230:231], v[232:233], s[40:41] op_sel_hi:[1,1,0]
	s_nop 0
	v_pk_fma_f32 v[232:233], v[230:231], v[232:233], s[42:43] op_sel_hi:[1,1,0]
	s_nop 0
	v_pk_fma_f32 v[230:231], v[230:231], v[232:233], s[44:45] op_sel_hi:[1,1,0]
	s_nop 0
	v_pk_mul_f32 v[176:177], v[176:177], v[230:231]
	s_nop 0
	v_pk_fma_f32 v[172:173], v[172:173], v[176:177], v[172:173]
	s_nop 0
	v_mul_f32_e32 v169, v68, v172
	v_mul_f32_e32 v172, v69, v173
	v_mul_f32_e32 v185, v188, v172
	v_lshlrev_b32_e32 v172, 16, v183
	v_and_b32_e32 v173, 0xffff0000, v183
	v_pk_fma_f32 v[170:171], v[134:135], v[172:173], v[170:171]
	v_mul_f32_e32 v169, v188, v169
	v_pk_mul_f32 v[172:173], v[170:171], s[26:27] op_sel_hi:[1,0]
	v_pk_mul_f32 v[170:171], v[170:171], 0.5 op_sel_hi:[1,0]
	v_med3_f32 v172, v172, s71, v224
	v_med3_f32 v173, v173, s71, v224
	v_pk_mul_f32 v[176:177], v[172:173], v[172:173]
	s_nop 0
	v_pk_fma_f32 v[182:183], v[176:177], s[28:29], v[148:149] op_sel_hi:[1,0,0] neg_lo:[1,0,0] neg_hi:[1,0,0]
	s_nop 0
	v_pk_fma_f32 v[182:183], v[176:177], v[182:183], s[34:35] op_sel_hi:[1,1,0]
	s_nop 0
	v_pk_fma_f32 v[182:183], v[176:177], v[182:183], s[36:37] op_sel_hi:[1,1,0]
	s_nop 0
	v_pk_fma_f32 v[182:183], v[176:177], v[182:183], s[38:39] op_sel_hi:[1,1,0]
	s_nop 0
	v_pk_fma_f32 v[182:183], v[176:177], v[182:183], s[40:41] op_sel_hi:[1,1,0]
	s_nop 0
	v_pk_fma_f32 v[182:183], v[176:177], v[182:183], s[42:43] op_sel_hi:[1,1,0]
	s_nop 0
	v_pk_fma_f32 v[176:177], v[176:177], v[182:183], s[44:45] op_sel_hi:[1,1,0]
	s_nop 0
	v_pk_mul_f32 v[172:173], v[172:173], v[176:177]
	s_nop 0
	v_pk_fma_f32 v[170:171], v[170:171], v[172:173], v[170:171]
	s_nop 0
	v_mul_f32_e32 v170, v70, v170
	v_mul_f32_e32 v172, v188, v170
	v_mul_f32_e32 v170, v71, v171
	v_mul_f32_e32 v171, v188, v170
	v_cvt_pk_bf16_f32 v170, v169, v185
	v_cvt_pk_bf16_f32 v171, v172, v171
	s_waitcnt vmcnt(4)
	v_mov_b32_dpp v169, v228 row_ror:1 row_mask:0xf bank_mask:0xf bound_ctrl:1
	global_store_dwordx2 v[174:175], v[170:171], off sc1
	v_mov_b32_dpp v171, v228 row_ror:2 row_mask:0xf bank_mask:0xf bound_ctrl:1
	v_mov_b32_dpp v169, v228 row_shr:1 row_mask:0xf bank_mask:0xf
	v_mov_b32_dpp v170, v229 row_ror:1 row_mask:0xf bank_mask:0xf bound_ctrl:1
	v_mov_b32_dpp v171, v228 row_shr:2 row_mask:0xf bank_mask:0xf
	v_lshlrev_b32_e32 v173, 16, v169
	v_and_b32_e32 v169, 0xffff0000, v169
	v_mov_b32_dpp v170, v229 row_shr:1 row_mask:0xf bank_mask:0xf
	v_mov_b32_dpp v172, v229 row_ror:2 row_mask:0xf bank_mask:0xf bound_ctrl:1
	v_lshlrev_b32_e32 v176, 16, v171
	v_and_b32_e32 v177, 0xffff0000, v171
	s_waitcnt vmcnt(1)
	v_cndmask_b32_e64 v171, v169, v213, s[6:7]
	v_cndmask_b32_e32 v169, v178, v212, vcc
	v_cndmask_b32_e32 v178, v179, v213, vcc
	v_mov_b32_dpp v172, v229 row_shr:2 row_mask:0xf bank_mask:0xf
	v_lshlrev_b32_e32 v174, 16, v170
	v_and_b32_e32 v175, 0xffff0000, v170
	v_cndmask_b32_e64 v177, v177, v178, s[0:1]
	v_cndmask_b32_e64 v176, v176, v169, s[0:1]
	v_lshlrev_b32_e32 v182, 16, v172
	v_and_b32_e32 v183, 0xffff0000, v172
	v_cndmask_b32_e64 v170, v173, v212, s[6:7]
	v_cndmask_b32_e64 v173, v175, v215, s[6:7]
	v_cndmask_b32_e64 v172, v174, v214, s[6:7]
	v_cndmask_b32_e32 v174, v180, v214, vcc
	v_cndmask_b32_e32 v175, v181, v215, vcc
	v_pk_fma_f32 v[176:177], v[140:141], v[176:177], v[144:145]
	v_cndmask_b32_e64 v175, v183, v175, s[0:1]
	v_cndmask_b32_e64 v174, v182, v174, s[0:1]
	v_lshlrev_b32_e32 v180, 16, v228
	v_and_b32_e32 v181, 0xffff0000, v228
	v_pk_fma_f32 v[170:171], v[136:137], v[170:171], v[176:177]
	v_pk_fma_f32 v[174:175], v[142:143], v[174:175], v[146:147]
	v_pk_fma_f32 v[170:171], v[132:133], v[180:181], v[170:171]
	v_pk_fma_f32 v[172:173], v[138:139], v[172:173], v[174:175]
	v_pk_mul_f32 v[174:175], v[170:171], s[26:27] op_sel_hi:[1,0]
	v_pk_mul_f32 v[170:171], v[170:171], 0.5 op_sel_hi:[1,0]
	v_med3_f32 v174, v174, s71, v224
	v_med3_f32 v175, v175, s71, v224
	v_pk_mul_f32 v[176:177], v[174:175], v[174:175]
	v_lshl_add_u64 v[178:179], v[154:155], 0, v[162:163]
	v_pk_fma_f32 v[180:181], v[176:177], s[28:29], v[148:149] op_sel_hi:[1,0,0] neg_lo:[1,0,0] neg_hi:[1,0,0]
	v_mov_b32_dpp v185, v165 row_ror:2 row_mask:0xf bank_mask:0xf bound_ctrl:1
	v_pk_fma_f32 v[180:181], v[176:177], v[180:181], s[34:35] op_sel_hi:[1,1,0]
	s_nop 0
	v_pk_fma_f32 v[180:181], v[176:177], v[180:181], s[36:37] op_sel_hi:[1,1,0]
	v_mov_b32_dpp v185, v165 row_shr:2 row_mask:0xf bank_mask:0xf
	v_pk_fma_f32 v[180:181], v[176:177], v[180:181], s[38:39] op_sel_hi:[1,1,0]
	v_lshlrev_b32_e32 v211, 16, v185
	v_pk_fma_f32 v[180:181], v[176:177], v[180:181], s[40:41] op_sel_hi:[1,1,0]
	v_and_b32_e32 v185, 0xffff0000, v185
	v_pk_fma_f32 v[180:181], v[176:177], v[180:181], s[42:43] op_sel_hi:[1,1,0]
; __device__ __forceinline__ unsigned cvt_pk_bf16(float lo, float hi) { unsigned r; asm volatile("v_cvt_pk_bf16_f32 %0, %1, %2" : "=v"(r) : "v"(lo), "v"(hi)); return r; }
;     static __device__ __forceinline__ void finish(const float (&g0)[4], const float (&g1)[4], const float (&g2)[4], const float (&w0)[4], const float (&w1)[4], const float (&w2)[4], const float (&bb)[4],
;                                                   const f32x4 v, float rs, bf16_t* dst) {
;         float h[4];
; #pragma unroll
;         for (int j = 0; j < 4; j += 2) {
;             const f32x2 gc = (f32x2){bb[j] + w0[j] * g2[j] + w1[j] * g1[j] + w2[j] * g0[j], bb[j + 1] + w0[j + 1] * g2[j + 1] + w1[j + 1] * g1[j + 1] + w2[j + 1] * g0[j + 1]};
;             const f32x2 ge = gelu_pk(gc); h[j] = ge.x * v[j] * rs; h[j + 1] = ge.y * v[j + 1] * rs; }
;         u32x2 w; w.x = cvt_pk_bf16(h[0], h[1]); w.y = cvt_pk_bf16(h[2], h[3]);
;         *(u32x2*)dst = w;
;     }
;     __device__ __forceinline__ void operator()(const f32x4 (&acc)[2][2][4][2], const Unit& u, int wr, int wc, int fr, int fq) const {
;     ...
;                 u32x2 gq[4];
; #pragma unroll
;                 for (int m = 0; m < 4; ++m) { const int row = row0 + m * 16; gq[m] = *(const u32x2*)(G + (size_t)row * 2816 + col); }
; #pragma unroll
;                 for (int mh = 0; mh < 4; mh += 2) {
;                 f32x4 c0[4], c1[4];
; #pragma unroll
;                 for (int m = mh; m < mh + 2; ++m) { const int row = row0 + m * 16; const float* cx = ctx + (size_t)((row - 32768) >> 3) * 2 * 2816 + col;
;                     c0[m] = *(const f32x4*)cx; c1[m] = *(const f32x4*)(cx + 2816); }
; #pragma unroll
;                 for (int m = mh; m < mh + 2; ++m) { const int row = row0 + m * 16; const u32x2 cur = gq[m];
;                     const u32x2 q1 = dpp_prev<1>(cur, cur), q2 = dpp_prev<2>(cur, cur);
;                     float g0[4], g1[4], g2[4]; unpk4(cur, g0); unpk4(q1, g1); unpk4(q2, g2);
; #pragma unroll
;                     for (int j = 0; j < 4; ++j) { const float x1 = c1[m][j], x0 = c0[m][j];
;                         if (i < 1) g1[j] = x1;
;                         if (i < 2) g2[j] = (i == 1) ? x1 : x0; }
;                     finish(g0, g1, g2, w0, w1, w2, bb, acc[0][bj][m][hv], rs8[0][m], H + (size_t)row * 2816 + col); }
;                 }
	s_nop 0
	v_pk_fma_f32 v[176:177], v[176:177], v[180:181], s[44:45] op_sel_hi:[1,1,0]
	s_nop 0
	v_pk_mul_f32 v[174:175], v[174:175], v[176:177]
	s_nop 0
	v_pk_fma_f32 v[170:171], v[170:171], v[174:175], v[170:171]
	s_nop 0
	v_mul_f32_e32 v169, v56, v170
	v_mul_f32_e32 v170, v57, v171
	v_mul_f32_e32 v180, v186, v170
	v_lshlrev_b32_e32 v170, 16, v229
	v_and_b32_e32 v171, 0xffff0000, v229
	v_pk_fma_f32 v[170:171], v[134:135], v[170:171], v[172:173]
	v_mul_f32_e32 v169, v186, v169
	v_pk_mul_f32 v[172:173], v[170:171], s[26:27] op_sel_hi:[1,0]
	v_pk_mul_f32 v[170:171], v[170:171], 0.5 op_sel_hi:[1,0]
	v_med3_f32 v172, v172, s71, v224
	v_med3_f32 v173, v173, s71, v224
	v_pk_mul_f32 v[174:175], v[172:173], v[172:173]
	s_nop 0
	v_pk_fma_f32 v[176:177], v[174:175], s[28:29], v[148:149] op_sel_hi:[1,0,0] neg_lo:[1,0,0] neg_hi:[1,0,0]
	s_nop 0
	v_pk_fma_f32 v[176:177], v[174:175], v[176:177], s[34:35] op_sel_hi:[1,1,0]
	s_nop 0
	v_pk_fma_f32 v[176:177], v[174:175], v[176:177], s[36:37] op_sel_hi:[1,1,0]
	s_nop 0
	v_pk_fma_f32 v[176:177], v[174:175], v[176:177], s[38:39] op_sel_hi:[1,1,0]
	s_nop 0
	v_pk_fma_f32 v[176:177], v[174:175], v[176:177], s[40:41] op_sel_hi:[1,1,0]
	s_nop 0
	v_pk_fma_f32 v[176:177], v[174:175], v[176:177], s[42:43] op_sel_hi:[1,1,0]
	s_nop 0
	v_pk_fma_f32 v[174:175], v[174:175], v[176:177], s[44:45] op_sel_hi:[1,1,0]
	s_nop 0
	v_pk_mul_f32 v[172:173], v[172:173], v[174:175]
	v_mad_i64_i32 v[174:175], s[8:9], v167, s70, v[226:227]
	v_pk_fma_f32 v[170:171], v[170:171], v[172:173], v[170:171]
	s_nop 0
	v_mul_f32_e32 v170, v58, v170
	v_mul_f32_e32 v172, v186, v170
	v_mul_f32_e32 v170, v59, v171
	v_mul_f32_e32 v171, v186, v170
	v_cvt_pk_bf16_f32 v170, v169, v180
	v_cvt_pk_bf16_f32 v171, v172, v171
	global_store_dwordx2 v[178:179], v[170:171], off sc1
	v_add_co_u32_e64 v170, s[8:9], s41, v174
	v_mov_b32_dpp v169, v164 row_ror:1 row_mask:0xf bank_mask:0xf bound_ctrl:1
	s_nop 0
	v_addc_co_u32_e64 v171, s[8:9], 0, v175, s[8:9]
	global_load_dwordx4 v[170:173], v[170:171], off offset:3072
	s_nop 0
	global_load_dwordx4 v[174:177], v[174:175], off
	v_mad_i64_i32 v[178:179], s[8:9], v168, s70, v[226:227]
	v_add_co_u32_e64 v182, s[8:9], s41, v178
	v_mov_b32_dpp v169, v164 row_shr:1 row_mask:0xf bank_mask:0xf
	s_nop 0
	v_addc_co_u32_e64 v183, s[8:9], 0, v179, s[8:9]
	global_load_dwordx4 v[178:181], v[178:179], off
	s_nop 0
	global_load_dwordx4 v[212:215], v[182:183], off offset:3072
	v_mov_b32_dpp v182, v165 row_ror:1 row_mask:0xf bank_mask:0xf bound_ctrl:1
	v_mov_b32_dpp v183, v164 row_ror:2 row_mask:0xf bank_mask:0xf bound_ctrl:1
	v_lshlrev_b32_e32 v187, 16, v169
	v_mov_b32_dpp v182, v165 row_shr:1 row_mask:0xf bank_mask:0xf
	v_mov_b32_dpp v183, v164 row_shr:2 row_mask:0xf bank_mask:0xf
	v_and_b32_e32 v169, 0xffff0000, v169
	v_lshlrev_b32_e32 v189, 16, v182
	v_and_b32_e32 v191, 0xffff0000, v182
	v_lshlrev_b32_e32 v193, 16, v183
	v_and_b32_e32 v195, 0xffff0000, v183
	s_waitcnt vmcnt(3)
	v_cndmask_b32_e64 v183, v169, v171, s[6:7]
	s_waitcnt vmcnt(2)
	v_cndmask_b32_e32 v169, v174, v170, vcc
	v_cndmask_b32_e32 v174, v175, v171, vcc
	v_cndmask_b32_e64 v182, v187, v170, s[6:7]
	v_cndmask_b32_e64 v227, v191, v173, s[6:7]
	v_cndmask_b32_e64 v226, v189, v172, s[6:7]
	v_cndmask_b32_e32 v170, v176, v172, vcc
	v_cndmask_b32_e32 v171, v177, v173, vcc
	v_cndmask_b32_e64 v173, v195, v174, s[0:1]
	v_cndmask_b32_e64 v172, v193, v169, s[0:1]
	v_pk_fma_f32 v[172:173], v[140:141], v[172:173], v[144:145]
	v_lshlrev_b32_e32 v176, 16, v164
	v_and_b32_e32 v177, 0xffff0000, v164
	v_pk_fma_f32 v[172:173], v[136:137], v[182:183], v[172:173]
	v_cndmask_b32_e64 v171, v185, v171, s[0:1]
	v_pk_fma_f32 v[172:173], v[132:133], v[176:177], v[172:173]
	v_cndmask_b32_e64 v170, v211, v170, s[0:1]
	v_pk_mul_f32 v[176:177], v[172:173], s[26:27] op_sel_hi:[1,0]
	v_pk_fma_f32 v[170:171], v[142:143], v[170:171], v[146:147]
	v_med3_f32 v176, v176, s71, v224
	v_med3_f32 v177, v177, s71, v224
	v_pk_mul_f32 v[182:183], v[176:177], v[176:177]
	v_pk_fma_f32 v[170:171], v[138:139], v[226:227], v[170:171]
	v_pk_fma_f32 v[226:227], v[182:183], s[28:29], v[148:149] op_sel_hi:[1,0,0] neg_lo:[1,0,0] neg_hi:[1,0,0]
	v_pk_mul_f32 v[172:173], v[172:173], 0.5 op_sel_hi:[1,0]
	v_pk_fma_f32 v[226:227], v[182:183], v[226:227], s[34:35] op_sel_hi:[1,1,0]
	v_lshl_add_u64 v[174:175], v[156:157], 0, v[162:163]
	v_pk_fma_f32 v[226:227], v[182:183], v[226:227], s[36:37] op_sel_hi:[1,1,0]
	v_lshl_add_u64 v[162:163], v[158:159], 0, v[162:163]
	v_pk_fma_f32 v[226:227], v[182:183], v[226:227], s[38:39] op_sel_hi:[1,1,0]
	s_nop 0
	v_pk_fma_f32 v[226:227], v[182:183], v[226:227], s[40:41] op_sel_hi:[1,1,0]
	s_nop 0
	v_pk_fma_f32 v[226:227], v[182:183], v[226:227], s[42:43] op_sel_hi:[1,1,0]
	s_nop 0
	v_pk_fma_f32 v[182:183], v[182:183], v[226:227], s[44:45] op_sel_hi:[1,1,0]
	s_nop 0
	v_pk_mul_f32 v[176:177], v[176:177], v[182:183]
	s_nop 0
	v_pk_fma_f32 v[172:173], v[172:173], v[176:177], v[172:173]
	s_nop 0
	v_mul_f32_e32 v164, v48, v172
	v_mul_f32_e32 v169, v184, v164
	v_mul_f32_e32 v164, v49, v173
	v_mul_f32_e32 v182, v184, v164
	v_lshlrev_b32_e32 v164, 16, v165
	v_and_b32_e32 v165, 0xffff0000, v165
	v_pk_fma_f32 v[164:165], v[134:135], v[164:165], v[170:171]
	s_nop 0
	v_pk_mul_f32 v[170:171], v[164:165], s[26:27] op_sel_hi:[1,0]
	v_pk_mul_f32 v[164:165], v[164:165], 0.5 op_sel_hi:[1,0]
	v_med3_f32 v170, v170, s71, v224
	v_med3_f32 v171, v171, s71, v224
	v_pk_mul_f32 v[172:173], v[170:171], v[170:171]
	s_nop 0
	v_pk_fma_f32 v[176:177], v[172:173], s[28:29], v[148:149] op_sel_hi:[1,0,0] neg_lo:[1,0,0] neg_hi:[1,0,0]
	s_nop 0
	v_pk_fma_f32 v[176:177], v[172:173], v[176:177], s[34:35] op_sel_hi:[1,1,0]
	s_nop 0
	v_pk_fma_f32 v[176:177], v[172:173], v[176:177], s[36:37] op_sel_hi:[1,1,0]
	s_nop 0
	v_pk_fma_f32 v[176:177], v[172:173], v[176:177], s[38:39] op_sel_hi:[1,1,0]
	s_nop 0
	v_pk_fma_f32 v[176:177], v[172:173], v[176:177], s[40:41] op_sel_hi:[1,1,0]
	s_nop 0
	v_pk_fma_f32 v[176:177], v[172:173], v[176:177], s[42:43] op_sel_hi:[1,1,0]
	s_nop 0
	v_pk_fma_f32 v[172:173], v[172:173], v[176:177], s[44:45] op_sel_hi:[1,1,0]
	s_waitcnt vmcnt(0)
;     static __device__ __forceinline__ void finish(const float (&g0)[4], const float (&g1)[4], const float (&g2)[4], const float (&w0)[4], const float (&w1)[4], const float (&w2)[4], const float (&bb)[4],
;                                                   const f32x4 v, float rs, bf16_t* dst) {
;         float h[4];
; #pragma unroll
;         for (int j = 0; j < 4; j += 2) {
;             const f32x2 gc = (f32x2){bb[j] + w0[j] * g2[j] + w1[j] * g1[j] + w2[j] * g0[j], bb[j + 1] + w0[j + 1] * g2[j + 1] + w1[j + 1] * g1[j + 1] + w2[j + 1] * g0[j + 1]};
;             const f32x2 ge = gelu_pk(gc); h[j] = ge.x * v[j] * rs; h[j + 1] = ge.y * v[j + 1] * rs; }
;         u32x2 w; w.x = cvt_pk_bf16(h[0], h[1]); w.y = cvt_pk_bf16(h[2], h[3]);
;         *(u32x2*)dst = w;
;     }
;     __device__ __forceinline__ void operator()(const f32x4 (&acc)[2][2][4][2], const Unit& u, int wr, int wc, int fr, int fq) const {
;     ...
;           for (int hv = 0; hv < 2; ++hv) {
;             const int col = u.pn * BM + bj * HALF + wc * 32 + 8 * fq + 4 * hv;
;             float w0[4], w1[4], w2[4], bb[4];
;             ld4f(cw + col, w0); ld4f(cw + 2816 + col, w1); ld4f(cw + 2 * 2816 + col, w2); ld4f(cb + col, bb);
;             {
;                 const int i = fr & 7;
;                 u32x2 gq[4];
; #pragma unroll
;                 for (int m = 0; m < 4; ++m) { const int row = row0 + m * 16; gq[m] = *(const u32x2*)(G + (size_t)row * 2816 + col); }
; #pragma unroll
;                 for (int mh = 0; mh < 4; mh += 2) {
;                 f32x4 c0[4], c1[4];
; #pragma unroll
;                 for (int m = mh; m < mh + 2; ++m) { const int row = row0 + m * 16; const float* cx = ctx + (size_t)((row - 32768) >> 3) * 2 * 2816 + col;
;                     c0[m] = *(const f32x4*)cx; c1[m] = *(const f32x4*)(cx + 2816); }
; #pragma unroll
;                 for (int m = mh; m < mh + 2; ++m) { const int row = row0 + m * 16; const u32x2 cur = gq[m];
;                     const u32x2 q1 = dpp_prev<1>(cur, cur), q2 = dpp_prev<2>(cur, cur);
;                     float g0[4], g1[4], g2[4]; unpk4(cur, g0); unpk4(q1, g1); unpk4(q2, g2);
; #pragma unroll
;                     for (int j = 0; j < 4; ++j) { const float x1 = c1[m][j], x0 = c0[m][j];
;                         if (i < 1) g1[j] = x1;
;                         if (i < 2) g2[j] = (i == 1) ? x1 : x0; }
	v_cndmask_b32_e32 v177, v178, v212, vcc
	v_pk_mul_f32 v[170:171], v[170:171], v[172:173]
	v_cndmask_b32_e32 v178, v179, v213, vcc
	v_pk_fma_f32 v[164:165], v[164:165], v[170:171], v[164:165]
	s_nop 0
	v_mul_f32_e32 v164, v50, v164
	v_mul_f32_e32 v170, v184, v164
	v_mul_f32_e32 v164, v51, v165
	v_mul_f32_e32 v165, v184, v164
	v_cvt_pk_bf16_f32 v164, v169, v182
	v_cvt_pk_bf16_f32 v165, v170, v165
	global_store_dwordx2 v[174:175], v[164:165], off sc1
	v_mov_b32_dpp v169, v160 row_ror:2 row_mask:0xf bank_mask:0xf bound_ctrl:1
	v_mov_b32_dpp v165, v161 row_ror:1 row_mask:0xf bank_mask:0xf bound_ctrl:1
	v_mov_b32_dpp v170, v161 row_ror:2 row_mask:0xf bank_mask:0xf bound_ctrl:1
	v_mov_b32_dpp v164, v160 row_ror:1 row_mask:0xf bank_mask:0xf bound_ctrl:1
	v_mov_b32_dpp v165, v161 row_shr:1 row_mask:0xf bank_mask:0xf
	v_mov_b32_dpp v169, v160 row_shr:2 row_mask:0xf bank_mask:0xf
	v_mov_b32_dpp v170, v161 row_shr:2 row_mask:0xf bank_mask:0xf
	v_lshlrev_b32_e32 v172, 16, v165
	v_mov_b32_dpp v164, v160 row_shr:1 row_mask:0xf bank_mask:0xf
	v_lshlrev_b32_e32 v174, 16, v169
	v_and_b32_e32 v169, 0xffff0000, v169
	v_lshlrev_b32_e32 v175, 16, v170
	v_and_b32_e32 v176, 0xffff0000, v170
	v_cndmask_b32_e64 v170, v172, v214, s[6:7]
	v_cndmask_b32_e32 v172, v180, v214, vcc
	v_lshlrev_b32_e32 v171, 16, v164
	v_and_b32_e32 v164, 0xffff0000, v164
	v_and_b32_e32 v173, 0xffff0000, v165
	v_cndmask_b32_e64 v172, v175, v172, s[0:1]
	v_cndmask_b32_e64 v175, v169, v178, s[0:1]
	v_cndmask_b32_e64 v174, v174, v177, s[0:1]
	v_cndmask_b32_e64 v165, v164, v213, s[6:7]
	v_cndmask_b32_e64 v164, v171, v212, s[6:7]
	v_cndmask_b32_e64 v171, v173, v215, s[6:7]
	v_cndmask_b32_e32 v173, v181, v215, vcc
	v_pk_fma_f32 v[140:141], v[140:141], v[174:175], v[144:145]
	v_cndmask_b32_e64 v173, v176, v173, s[0:1]
	v_lshlrev_b32_e32 v176, 16, v160
	v_and_b32_e32 v177, 0xffff0000, v160
	v_pk_fma_f32 v[136:137], v[136:137], v[164:165], v[140:141]
	v_pk_fma_f32 v[142:143], v[142:143], v[172:173], v[146:147]
	v_pk_fma_f32 v[132:133], v[132:133], v[176:177], v[136:137]
	v_pk_fma_f32 v[138:139], v[138:139], v[170:171], v[142:143]
	v_pk_mul_f32 v[136:137], v[132:133], s[26:27] op_sel_hi:[1,0]
	v_pk_mul_f32 v[132:133], v[132:133], 0.5 op_sel_hi:[1,0]
	v_med3_f32 v136, v136, s71, v224
	v_med3_f32 v137, v137, s71, v224
	v_pk_mul_f32 v[140:141], v[136:137], v[136:137]
	s_nop 0
	v_pk_fma_f32 v[142:143], v[140:141], s[28:29], v[148:149] op_sel_hi:[1,0,0] neg_lo:[1,0,0] neg_hi:[1,0,0]
	s_nop 0
	v_pk_fma_f32 v[142:143], v[140:141], v[142:143], s[34:35] op_sel_hi:[1,1,0]
	s_nop 0
	v_pk_fma_f32 v[142:143], v[140:141], v[142:143], s[36:37] op_sel_hi:[1,1,0]
	s_nop 0
	v_pk_fma_f32 v[142:143], v[140:141], v[142:143], s[38:39] op_sel_hi:[1,1,0]
	s_nop 0
	v_pk_fma_f32 v[142:143], v[140:141], v[142:143], s[40:41] op_sel_hi:[1,1,0]
	s_nop 0
	v_pk_fma_f32 v[142:143], v[140:141], v[142:143], s[42:43] op_sel_hi:[1,1,0]
	s_nop 0
	v_pk_fma_f32 v[140:141], v[140:141], v[142:143], s[44:45] op_sel_hi:[1,1,0]
	s_nop 0
	v_pk_mul_f32 v[136:137], v[136:137], v[140:141]
	s_nop 0
	v_pk_fma_f32 v[132:133], v[132:133], v[136:137], v[132:133]
	s_nop 0
	v_mul_f32_e32 v132, v40, v132
	v_mul_f32_e32 v140, v2, v132
	v_mul_f32_e32 v132, v41, v133
	v_mul_f32_e32 v141, v2, v132
	v_lshlrev_b32_e32 v132, 16, v161
	v_and_b32_e32 v133, 0xffff0000, v161
	v_pk_fma_f32 v[132:133], v[134:135], v[132:133], v[138:139]
	s_nop 0
	v_pk_mul_f32 v[134:135], v[132:133], s[26:27] op_sel_hi:[1,0]
	v_pk_mul_f32 v[132:133], v[132:133], 0.5 op_sel_hi:[1,0]
	v_med3_f32 v134, v134, s71, v224
	v_med3_f32 v135, v135, s71, v224
	v_pk_mul_f32 v[136:137], v[134:135], v[134:135]
	s_nop 0
	v_pk_fma_f32 v[138:139], v[136:137], s[28:29], v[148:149] op_sel_hi:[1,0,0] neg_lo:[1,0,0] neg_hi:[1,0,0]
	s_nop 0
	v_pk_fma_f32 v[138:139], v[136:137], v[138:139], s[34:35] op_sel_hi:[1,1,0]
	s_nop 0
	v_pk_fma_f32 v[138:139], v[136:137], v[138:139], s[36:37] op_sel_hi:[1,1,0]
	s_nop 0
	v_pk_fma_f32 v[138:139], v[136:137], v[138:139], s[38:39] op_sel_hi:[1,1,0]
	s_nop 0
	v_pk_fma_f32 v[138:139], v[136:137], v[138:139], s[40:41] op_sel_hi:[1,1,0]
	s_nop 0
	v_pk_fma_f32 v[138:139], v[136:137], v[138:139], s[42:43] op_sel_hi:[1,1,0]
	s_nop 0
	v_pk_fma_f32 v[136:137], v[136:137], v[138:139], s[44:45] op_sel_hi:[1,1,0]
	s_nop 0
	v_pk_mul_f32 v[134:135], v[134:135], v[136:137]
	s_nop 0
	v_pk_fma_f32 v[132:133], v[132:133], v[134:135], v[132:133]
	s_nop 0
	v_mul_f32_e32 v132, v42, v132
	v_mul_f32_e32 v134, v2, v132
	v_mul_f32_e32 v132, v43, v133
	v_mul_f32_e32 v133, v2, v132
	v_cvt_pk_bf16_f32 v132, v140, v141
	v_cvt_pk_bf16_f32 v133, v134, v133
	global_store_dwordx2 v[162:163], v[132:133], off sc1
	v_add_u32_e32 v132, 0x84, v150
	v_ashrrev_i32_e32 v133, 31, v132
	v_lshlrev_b64 v[160:161], 1, v[132:133]
	v_lshl_add_u64 v[162:163], s[56:57], 0, v[160:161]
	v_lshlrev_b64 v[132:133], 2, v[132:133]
	v_mad_i64_i32 v[134:135], s[8:9], v210, s67, v[162:163]
	v_lshl_add_u64 v[182:183], s[16:17], 0, v[132:133]
	global_load_dwordx2 v[164:165], v[134:135], off
	v_mad_i64_i32 v[134:135], s[8:9], v151, s70, v[182:183]
	v_add_co_u32_e64 v136, s[8:9], s41, v134
	v_lshl_add_u64 v[152:153], v[152:153], 0, v[160:161]
	s_nop 0
	v_addc_co_u32_e64 v137, s[8:9], 0, v135, s[8:9]
	global_load_dwordx4 v[170:173], v[136:137], off offset:3072
	global_load_dwordx4 v[174:177], v[134:135], off
	v_lshl_add_u64 v[134:135], s[12:13], 0, v[132:133]
	global_load_dwordx4 v[140:143], v[134:135], off
	v_lshl_add_u64 v[134:135], s[14:15], 0, v[132:133]
	global_load_dwordx4 v[144:147], v[134:135], off
	v_lshl_add_u64 v[134:135], s[18:19], 0, v[132:133]
	global_load_dwordx4 v[136:139], v[134:135], off
	v_lshl_add_u64 v[132:133], s[20:21], 0, v[132:133]
	global_load_dwordx4 v[132:135], v[132:133], off
	v_mad_i64_i32 v[150:151], s[8:9], v194, s67, v[162:163]
	v_mad_i64_i32 v[178:179], s[8:9], v192, s67, v[162:163]
	v_mad_i64_i32 v[180:181], s[8:9], v190, s67, v[162:163]
	global_load_dwordx2 v[226:227], v[150:151], off
	global_load_dwordx2 v[162:163], v[178:179], off
	s_nop 0
	global_load_dwordx2 v[150:151], v[180:181], off
	v_mad_i64_i32 v[178:179], s[8:9], v166, s70, v[182:183]
	v_add_co_u32_e64 v212, s[8:9], s41, v178
	v_lshl_add_u64 v[154:155], v[154:155], 0, v[160:161]
	s_nop 0
	v_addc_co_u32_e64 v213, s[8:9], 0, v179, s[8:9]
	global_load_dwordx4 v[178:181], v[178:179], off
	s_nop 0
	global_load_dwordx4 v[212:215], v[212:213], off offset:3072
	v_lshl_add_u64 v[156:157], v[156:157], 0, v[160:161]
	v_lshl_add_u64 v[158:159], v[158:159], 0, v[160:161]
	s_waitcnt vmcnt(11)
; __device__ __forceinline__ unsigned cvt_pk_bf16(float lo, float hi) { unsigned r; asm volatile("v_cvt_pk_bf16_f32 %0, %1, %2" : "=v"(r) : "v"(lo), "v"(hi)); return r; }
;     static __device__ __forceinline__ void unpk4(const u32x2 w, float (&o)[4]) { o[0] = bf_lo(w.x); o[1] = bf_hi(w.x); o[2] = bf_lo(w.y); o[3] = bf_hi(w.y); }
;     template <int N> static __device__ __forceinline__ u32x2 dpp_prev(const u32x2 pv, const u32x2 cur) { u32x2 r; r.x = dpp_prev1<N>(pv.x, cur.x); r.y = dpp_prev1<N>(pv.y, cur.y); return r; }
;     static __device__ __forceinline__ void finish(const float (&g0)[4], const float (&g1)[4], const float (&g2)[4], const float (&w0)[4], const float (&w1)[4], const float (&w2)[4], const float (&bb)[4],
;                                                   const f32x4 v, float rs, bf16_t* dst) {
;         float h[4];
; #pragma unroll
;         for (int j = 0; j < 4; j += 2) {
;             const f32x2 gc = (f32x2){bb[j] + w0[j] * g2[j] + w1[j] * g1[j] + w2[j] * g0[j], bb[j + 1] + w0[j + 1] * g2[j + 1] + w1[j + 1] * g1[j + 1] + w2[j + 1] * g0[j + 1]};
;             const f32x2 ge = gelu_pk(gc); h[j] = ge.x * v[j] * rs; h[j + 1] = ge.y * v[j + 1] * rs; }
;         u32x2 w; w.x = cvt_pk_bf16(h[0], h[1]); w.y = cvt_pk_bf16(h[2], h[3]);
;         *(u32x2*)dst = w;
;     }
;     __device__ __forceinline__ void operator()(const f32x4 (&acc)[2][2][4][2], const Unit& u, int wr, int wc, int fr, int fq) const {
;     ...
;                 for (int m = mh; m < mh + 2; ++m) { const int row = row0 + m * 16; const u32x2 cur = gq[m];
;                     const u32x2 q1 = dpp_prev<1>(cur, cur), q2 = dpp_prev<2>(cur, cur);
;                     float g0[4], g1[4], g2[4]; unpk4(cur, g0); unpk4(q1, g1); unpk4(q2, g2);
; #pragma unroll
;                     for (int j = 0; j < 4; ++j) { const float x1 = c1[m][j], x0 = c0[m][j];
;                         if (i < 1) g1[j] = x1;
;                         if (i < 2) g2[j] = (i == 1) ? x1 : x0; }
;                     finish(g0, g1, g2, w0, w1, w2, bb, acc[0][bj][m][hv], rs8[0][m], H + (size_t)row * 2816 + col); }
	v_mov_b32_dpp v166, v164 row_ror:1 row_mask:0xf bank_mask:0xf bound_ctrl:1
	v_mov_b32_dpp v169, v165 row_ror:1 row_mask:0xf bank_mask:0xf bound_ctrl:1
	s_nop 0
	v_mov_b32_dpp v166, v164 row_shr:1 row_mask:0xf bank_mask:0xf
	v_mov_b32_dpp v185, v164 row_ror:2 row_mask:0xf bank_mask:0xf bound_ctrl:1
	v_mov_b32_dpp v169, v165 row_shr:1 row_mask:0xf bank_mask:0xf
	v_lshlrev_b32_e32 v189, 16, v166
	v_mov_b32_dpp v185, v164 row_shr:2 row_mask:0xf bank_mask:0xf
	v_and_b32_e32 v166, 0xffff0000, v166
	v_lshlrev_b32_e32 v191, 16, v169
	v_and_b32_e32 v169, 0xffff0000, v169
	v_lshlrev_b32_e32 v193, 16, v185
	v_and_b32_e32 v185, 0xffff0000, v185
	s_waitcnt vmcnt(10)
	v_cndmask_b32_e64 v229, v166, v171, s[6:7]
	v_cndmask_b32_e64 v231, v169, v173, s[6:7]
	s_waitcnt vmcnt(9)
	v_cndmask_b32_e32 v166, v174, v170, vcc
	v_cndmask_b32_e32 v169, v175, v171, vcc
	v_cndmask_b32_e64 v228, v189, v170, s[6:7]
	v_cndmask_b32_e64 v230, v191, v172, s[6:7]
	v_cndmask_b32_e32 v170, v176, v172, vcc
	v_cndmask_b32_e32 v171, v177, v173, vcc
	v_cndmask_b32_e64 v173, v185, v169, s[0:1]
	v_cndmask_b32_e64 v172, v193, v166, s[0:1]
	s_waitcnt vmcnt(7)
	v_pk_fma_f32 v[172:173], v[140:141], v[172:173], v[144:145]
	v_lshlrev_b32_e32 v174, 16, v164
	v_and_b32_e32 v175, 0xffff0000, v164
	s_waitcnt vmcnt(6)
	v_pk_fma_f32 v[172:173], v[136:137], v[228:229], v[172:173]
	v_mov_b32_dpp v187, v165 row_ror:2 row_mask:0xf bank_mask:0xf bound_ctrl:1
	s_waitcnt vmcnt(5)
	v_pk_fma_f32 v[172:173], v[132:133], v[174:175], v[172:173]
	s_waitcnt vmcnt(2)
	v_lshlrev_b32_e32 v160, 16, v150
	v_pk_mul_f32 v[174:175], v[172:173], s[26:27] op_sel_hi:[1,0]
	v_mov_b32_dpp v187, v165 row_shr:2 row_mask:0xf bank_mask:0xf
	v_med3_f32 v174, v174, s71, v224
	v_med3_f32 v175, v175, s71, v224
	v_pk_mul_f32 v[176:177], v[174:175], v[174:175]
	v_pk_mul_f32 v[172:173], v[172:173], 0.5 op_sel_hi:[1,0]
	v_pk_fma_f32 v[228:229], v[176:177], s[28:29], v[148:149] op_sel_hi:[1,0,0] neg_lo:[1,0,0] neg_hi:[1,0,0]
	v_lshlrev_b32_e32 v195, 16, v187
	v_pk_fma_f32 v[228:229], v[176:177], v[228:229], s[34:35] op_sel_hi:[1,1,0]
	v_and_b32_e32 v187, 0xffff0000, v187
	v_pk_fma_f32 v[228:229], v[176:177], v[228:229], s[36:37] op_sel_hi:[1,1,0]
	v_cndmask_b32_e64 v171, v187, v171, s[0:1]
	v_pk_fma_f32 v[228:229], v[176:177], v[228:229], s[38:39] op_sel_hi:[1,1,0]
	v_cndmask_b32_e64 v170, v195, v170, s[0:1]
	v_pk_fma_f32 v[228:229], v[176:177], v[228:229], s[40:41] op_sel_hi:[1,1,0]
	v_pk_fma_f32 v[170:171], v[142:143], v[170:171], v[146:147]
	v_pk_fma_f32 v[228:229], v[176:177], v[228:229], s[42:43] op_sel_hi:[1,1,0]
	v_pk_fma_f32 v[170:171], v[138:139], v[230:231], v[170:171]
	v_pk_fma_f32 v[176:177], v[176:177], v[228:229], s[44:45] op_sel_hi:[1,1,0]
	v_and_b32_e32 v161, 0xffff0000, v150
	v_pk_mul_f32 v[174:175], v[174:175], v[176:177]
	v_mov_b32_dpp v176, v162 row_ror:1 row_mask:0xf bank_mask:0xf bound_ctrl:1
	v_pk_fma_f32 v[172:173], v[172:173], v[174:175], v[172:173]
	v_mov_b32_dpp v177, v163 row_ror:1 row_mask:0xf bank_mask:0xf bound_ctrl:1
	v_mul_f32_e32 v164, v60, v172
	v_mul_f32_e32 v166, v188, v164
	v_mul_f32_e32 v164, v61, v173
	v_mul_f32_e32 v169, v188, v164
	v_lshlrev_b32_e32 v164, 16, v165
	v_and_b32_e32 v165, 0xffff0000, v165
	v_pk_fma_f32 v[164:165], v[134:135], v[164:165], v[170:171]
	v_mov_b32_dpp v176, v162 row_shr:1 row_mask:0xf bank_mask:0xf
	v_pk_mul_f32 v[170:171], v[164:165], s[26:27] op_sel_hi:[1,0]
	v_pk_mul_f32 v[164:165], v[164:165], 0.5 op_sel_hi:[1,0]
	v_med3_f32 v170, v170, s71, v224
	v_med3_f32 v171, v171, s71, v224
	v_pk_mul_f32 v[172:173], v[170:171], v[170:171]
	v_mov_b32_dpp v177, v163 row_shr:1 row_mask:0xf bank_mask:0xf
	v_pk_fma_f32 v[174:175], v[172:173], s[28:29], v[148:149] op_sel_hi:[1,0,0] neg_lo:[1,0,0] neg_hi:[1,0,0]
	s_nop 0
	v_pk_fma_f32 v[174:175], v[172:173], v[174:175], s[34:35] op_sel_hi:[1,1,0]
	s_nop 0
	v_pk_fma_f32 v[174:175], v[172:173], v[174:175], s[36:37] op_sel_hi:[1,1,0]
	s_nop 0
	v_pk_fma_f32 v[174:175], v[172:173], v[174:175], s[38:39] op_sel_hi:[1,1,0]
	s_nop 0
	v_pk_fma_f32 v[174:175], v[172:173], v[174:175], s[40:41] op_sel_hi:[1,1,0]
	s_nop 0
	v_pk_fma_f32 v[174:175], v[172:173], v[174:175], s[42:43] op_sel_hi:[1,1,0]
	s_nop 0
	v_pk_fma_f32 v[172:173], v[172:173], v[174:175], s[44:45] op_sel_hi:[1,1,0]
	s_waitcnt vmcnt(0)
; __device__ __forceinline__ unsigned cvt_pk_bf16(float lo, float hi) { unsigned r; asm volatile("v_cvt_pk_bf16_f32 %0, %1, %2" : "=v"(r) : "v"(lo), "v"(hi)); return r; }
;     static __device__ __forceinline__ void unpk4(const u32x2 w, float (&o)[4]) { o[0] = bf_lo(w.x); o[1] = bf_hi(w.x); o[2] = bf_lo(w.y); o[3] = bf_hi(w.y); }
;     template <int N> static __device__ __forceinline__ u32x2 dpp_prev(const u32x2 pv, const u32x2 cur) { u32x2 r; r.x = dpp_prev1<N>(pv.x, cur.x); r.y = dpp_prev1<N>(pv.y, cur.y); return r; }
;     static __device__ __forceinline__ void finish(const float (&g0)[4], const float (&g1)[4], const float (&g2)[4], const float (&w0)[4], const float (&w1)[4], const float (&w2)[4], const float (&bb)[4],
;                                                   const f32x4 v, float rs, bf16_t* dst) {
;         float h[4];
; #pragma unroll
;         for (int j = 0; j < 4; j += 2) {
;             const f32x2 gc = (f32x2){bb[j] + w0[j] * g2[j] + w1[j] * g1[j] + w2[j] * g0[j], bb[j + 1] + w0[j + 1] * g2[j + 1] + w1[j + 1] * g1[j + 1] + w2[j + 1] * g0[j + 1]};
;             const f32x2 ge = gelu_pk(gc); h[j] = ge.x * v[j] * rs; h[j + 1] = ge.y * v[j + 1] * rs; }
;         u32x2 w; w.x = cvt_pk_bf16(h[0], h[1]); w.y = cvt_pk_bf16(h[2], h[3]);
;         *(u32x2*)dst = w;
;     __device__ __forceinline__ void operator()(const f32x4 (&acc)[2][2][4][2], const Unit& u, int wr, int wc, int fr, int fq) const {
;     ...
;                 for (int m = mh; m < mh + 2; ++m) { const int row = row0 + m * 16; const float* cx = ctx + (size_t)((row - 32768) >> 3) * 2 * 2816 + col;
;                     c0[m] = *(const f32x4*)cx; c1[m] = *(const f32x4*)(cx + 2816); }
; #pragma unroll
;                 for (int m = mh; m < mh + 2; ++m) { const int row = row0 + m * 16; const u32x2 cur = gq[m];
;                     const u32x2 q1 = dpp_prev<1>(cur, cur), q2 = dpp_prev<2>(cur, cur);
;                     float g0[4], g1[4], g2[4]; unpk4(cur, g0); unpk4(q1, g1); unpk4(q2, g2);
; #pragma unroll
;                     for (int j = 0; j < 4; ++j) { const float x1 = c1[m][j], x0 = c0[m][j];
;                         if (i < 1) g1[j] = x1;
;                         if (i < 2) g2[j] = (i == 1) ? x1 : x0; }
;                     finish(g0, g1, g2, w0, w1, w2, bb, acc[0][bj][m][hv], rs8[0][m], H + (size_t)row * 2816 + col); }
	v_cndmask_b32_e32 v175, v181, v215, vcc
	v_pk_mul_f32 v[170:171], v[170:171], v[172:173]
	v_lshlrev_b32_e32 v181, 16, v177
	v_pk_fma_f32 v[164:165], v[164:165], v[170:171], v[164:165]
	s_nop 0
	v_mul_f32_e32 v164, v62, v164
	v_mul_f32_e32 v170, v188, v164
	v_mul_f32_e32 v164, v63, v165
	v_mul_f32_e32 v165, v188, v164
	v_cvt_pk_bf16_f32 v164, v166, v169
	v_cvt_pk_bf16_f32 v165, v170, v165
	global_store_dwordx2 v[152:153], v[164:165], off sc1
	v_mov_b32_dpp v152, v226 row_ror:1 row_mask:0xf bank_mask:0xf bound_ctrl:1
	v_mov_b32_dpp v153, v227 row_ror:1 row_mask:0xf bank_mask:0xf bound_ctrl:1
	v_mov_b32_dpp v164, v226 row_ror:2 row_mask:0xf bank_mask:0xf bound_ctrl:1
	v_mov_b32_dpp v152, v226 row_shr:1 row_mask:0xf bank_mask:0xf
	v_mov_b32_dpp v153, v227 row_shr:1 row_mask:0xf bank_mask:0xf
	v_mov_b32_dpp v164, v226 row_shr:2 row_mask:0xf bank_mask:0xf
	v_lshlrev_b32_e32 v166, 16, v152
	v_and_b32_e32 v152, 0xffff0000, v152
	v_lshlrev_b32_e32 v169, 16, v153
	v_mov_b32_dpp v165, v227 row_ror:2 row_mask:0xf bank_mask:0xf bound_ctrl:1
	v_and_b32_e32 v170, 0xffff0000, v153
	v_lshlrev_b32_e32 v172, 16, v164
	v_and_b32_e32 v173, 0xffff0000, v164
	v_cndmask_b32_e64 v153, v152, v213, s[6:7]
	v_cndmask_b32_e64 v152, v166, v212, s[6:7]
	v_cndmask_b32_e64 v164, v169, v214, s[6:7]
	v_cndmask_b32_e32 v166, v178, v212, vcc
	v_cndmask_b32_e32 v169, v179, v213, vcc
	v_mov_b32_dpp v165, v227 row_shr:2 row_mask:0xf bank_mask:0xf
	v_cndmask_b32_e64 v173, v173, v169, s[0:1]
	v_cndmask_b32_e64 v172, v172, v166, s[0:1]
	v_lshlrev_b32_e32 v174, 16, v165
	v_and_b32_e32 v171, 0xffff0000, v165
	v_cndmask_b32_e64 v165, v170, v215, s[6:7]
	v_cndmask_b32_e32 v170, v180, v214, vcc
	v_pk_fma_f32 v[172:173], v[140:141], v[172:173], v[144:145]
	v_cndmask_b32_e64 v171, v171, v175, s[0:1]
	v_cndmask_b32_e64 v170, v174, v170, s[0:1]
	v_lshlrev_b32_e32 v174, 16, v226
	v_and_b32_e32 v175, 0xffff0000, v226
	v_pk_fma_f32 v[152:153], v[136:137], v[152:153], v[172:173]
	v_pk_fma_f32 v[170:171], v[142:143], v[170:171], v[146:147]
	v_pk_fma_f32 v[152:153], v[132:133], v[174:175], v[152:153]
	v_pk_fma_f32 v[164:165], v[138:139], v[164:165], v[170:171]
	v_pk_mul_f32 v[170:171], v[152:153], s[26:27] op_sel_hi:[1,0]
	v_pk_mul_f32 v[152:153], v[152:153], 0.5 op_sel_hi:[1,0]
	v_med3_f32 v170, v170, s71, v224
	v_med3_f32 v171, v171, s71, v224
	v_pk_mul_f32 v[172:173], v[170:171], v[170:171]
	v_mov_b32_dpp v178, v162 row_ror:2 row_mask:0xf bank_mask:0xf bound_ctrl:1
	v_pk_fma_f32 v[174:175], v[172:173], s[28:29], v[148:149] op_sel_hi:[1,0,0] neg_lo:[1,0,0] neg_hi:[1,0,0]
	v_mov_b32_dpp v179, v163 row_ror:2 row_mask:0xf bank_mask:0xf bound_ctrl:1
	v_pk_fma_f32 v[174:175], v[172:173], v[174:175], s[34:35] op_sel_hi:[1,1,0]
	v_mov_b32_dpp v178, v162 row_shr:2 row_mask:0xf bank_mask:0xf
	v_pk_fma_f32 v[174:175], v[172:173], v[174:175], s[36:37] op_sel_hi:[1,1,0]
	v_mov_b32_dpp v179, v163 row_shr:2 row_mask:0xf bank_mask:0xf
	v_pk_fma_f32 v[174:175], v[172:173], v[174:175], s[38:39] op_sel_hi:[1,1,0]
	v_lshlrev_b32_e32 v180, 16, v176
	v_pk_fma_f32 v[174:175], v[172:173], v[174:175], s[40:41] op_sel_hi:[1,1,0]
	v_and_b32_e32 v176, 0xffff0000, v176
	v_pk_fma_f32 v[174:175], v[172:173], v[174:175], s[42:43] op_sel_hi:[1,1,0]
	v_and_b32_e32 v185, 0xffff0000, v178
	v_pk_fma_f32 v[172:173], v[172:173], v[174:175], s[44:45] op_sel_hi:[1,1,0]
	v_lshlrev_b32_e32 v187, 16, v179
	v_pk_mul_f32 v[170:171], v[170:171], v[172:173]
	v_and_b32_e32 v189, 0xffff0000, v179
	v_pk_fma_f32 v[152:153], v[152:153], v[170:171], v[152:153]
	s_nop 0
	v_mul_f32_e32 v152, v52, v152
	v_mul_f32_e32 v166, v186, v152
	v_mul_f32_e32 v152, v53, v153
	v_mul_f32_e32 v169, v186, v152
	v_lshlrev_b32_e32 v152, 16, v227
	v_and_b32_e32 v153, 0xffff0000, v227
	v_pk_fma_f32 v[152:153], v[134:135], v[152:153], v[164:165]
	s_nop 0
	v_pk_mul_f32 v[164:165], v[152:153], s[26:27] op_sel_hi:[1,0]
	v_pk_mul_f32 v[152:153], v[152:153], 0.5 op_sel_hi:[1,0]
	v_med3_f32 v164, v164, s71, v224
	v_med3_f32 v165, v165, s71, v224
	v_pk_mul_f32 v[170:171], v[164:165], v[164:165]
	s_nop 0
	v_pk_fma_f32 v[172:173], v[170:171], s[28:29], v[148:149] op_sel_hi:[1,0,0] neg_lo:[1,0,0] neg_hi:[1,0,0]
	s_nop 0
	v_pk_fma_f32 v[172:173], v[170:171], v[172:173], s[34:35] op_sel_hi:[1,1,0]
	s_nop 0
	v_pk_fma_f32 v[172:173], v[170:171], v[172:173], s[36:37] op_sel_hi:[1,1,0]
	s_nop 0
	v_pk_fma_f32 v[172:173], v[170:171], v[172:173], s[38:39] op_sel_hi:[1,1,0]
	s_nop 0
	v_pk_fma_f32 v[172:173], v[170:171], v[172:173], s[40:41] op_sel_hi:[1,1,0]
	s_nop 0
	v_pk_fma_f32 v[172:173], v[170:171], v[172:173], s[42:43] op_sel_hi:[1,1,0]
	s_nop 0
	v_pk_fma_f32 v[170:171], v[170:171], v[172:173], s[44:45] op_sel_hi:[1,1,0]
	s_nop 0
	v_pk_mul_f32 v[164:165], v[164:165], v[170:171]
	s_nop 0
	v_pk_fma_f32 v[152:153], v[152:153], v[164:165], v[152:153]
	s_nop 0
	v_mul_f32_e32 v152, v54, v152
	v_mul_f32_e32 v164, v186, v152
	v_mul_f32_e32 v152, v55, v153
	v_mul_f32_e32 v153, v186, v152
	v_cvt_pk_bf16_f32 v152, v166, v169
	v_cvt_pk_bf16_f32 v153, v164, v153
	v_mad_i64_i32 v[164:165], s[8:9], v167, s70, v[182:183]
	global_store_dwordx2 v[154:155], v[152:153], off sc1
	v_add_co_u32_e64 v152, s[8:9], s41, v164
	s_nop 1
	v_addc_co_u32_e64 v153, s[8:9], 0, v165, s[8:9]
	global_load_dwordx4 v[152:155], v[152:153], off offset:3072
	s_nop 0
	global_load_dwordx4 v[164:167], v[164:165], off
	v_mad_i64_i32 v[168:169], s[8:9], v168, s70, v[182:183]
	v_add_co_u32_e64 v172, s[8:9], s41, v168
	v_and_b32_e32 v182, 0xffff0000, v177
	s_nop 0
	v_addc_co_u32_e64 v173, s[8:9], 0, v169, s[8:9]
	global_load_dwordx4 v[168:171], v[168:169], off
	s_nop 0
	global_load_dwordx4 v[172:175], v[172:173], off offset:3072
	v_lshlrev_b32_e32 v183, 16, v178
	s_waitcnt vmcnt(3)
; __device__ __forceinline__ unsigned cvt_pk_bf16(float lo, float hi) { unsigned r; asm volatile("v_cvt_pk_bf16_f32 %0, %1, %2" : "=v"(r) : "v"(lo), "v"(hi)); return r; }
;     static __device__ __forceinline__ void unpk4(const u32x2 w, float (&o)[4]) { o[0] = bf_lo(w.x); o[1] = bf_hi(w.x); o[2] = bf_lo(w.y); o[3] = bf_hi(w.y); }
;     template <int N> static __device__ __forceinline__ u32x2 dpp_prev(const u32x2 pv, const u32x2 cur) { u32x2 r; r.x = dpp_prev1<N>(pv.x, cur.x); r.y = dpp_prev1<N>(pv.y, cur.y); return r; }
;     static __device__ __forceinline__ void finish(const float (&g0)[4], const float (&g1)[4], const float (&g2)[4], const float (&w0)[4], const float (&w1)[4], const float (&w2)[4], const float (&bb)[4],
;                                                   const f32x4 v, float rs, bf16_t* dst) {
;         float h[4];
; #pragma unroll
;         for (int j = 0; j < 4; j += 2) {
;             const f32x2 gc = (f32x2){bb[j] + w0[j] * g2[j] + w1[j] * g1[j] + w2[j] * g0[j], bb[j + 1] + w0[j + 1] * g2[j + 1] + w1[j + 1] * g1[j + 1] + w2[j + 1] * g0[j + 1]};
;             const f32x2 ge = gelu_pk(gc); h[j] = ge.x * v[j] * rs; h[j + 1] = ge.y * v[j + 1] * rs; }
;         u32x2 w; w.x = cvt_pk_bf16(h[0], h[1]); w.y = cvt_pk_bf16(h[2], h[3]);
;         *(u32x2*)dst = w;
;     __device__ __forceinline__ void operator()(const f32x4 (&acc)[2][2][4][2], const Unit& u, int wr, int wc, int fr, int fq) const {
;     ...
;                 for (int m = mh; m < mh + 2; ++m) { const int row = row0 + m * 16; const float* cx = ctx + (size_t)((row - 32768) >> 3) * 2 * 2816 + col;
;                     c0[m] = *(const f32x4*)cx; c1[m] = *(const f32x4*)(cx + 2816); }
; #pragma unroll
;                 for (int m = mh; m < mh + 2; ++m) { const int row = row0 + m * 16; const u32x2 cur = gq[m];
;                     const u32x2 q1 = dpp_prev<1>(cur, cur), q2 = dpp_prev<2>(cur, cur);
;                     float g0[4], g1[4], g2[4]; unpk4(cur, g0); unpk4(q1, g1); unpk4(q2, g2);
; #pragma unroll
;                     for (int j = 0; j < 4; ++j) { const float x1 = c1[m][j], x0 = c0[m][j];
;                         if (i < 1) g1[j] = x1;
;                         if (i < 2) g2[j] = (i == 1) ? x1 : x0; }
;                     finish(g0, g1, g2, w0, w1, w2, bb, acc[0][bj][m][hv], rs8[0][m], H + (size_t)row * 2816 + col); }
	v_cndmask_b32_e64 v177, v176, v153, s[6:7]
	s_waitcnt vmcnt(2)
	v_cndmask_b32_e32 v164, v164, v152, vcc
	v_cndmask_b32_e32 v165, v165, v153, vcc
	v_cndmask_b32_e64 v176, v180, v152, s[6:7]
	v_cndmask_b32_e64 v179, v182, v155, s[6:7]
	v_cndmask_b32_e64 v178, v181, v154, s[6:7]
	v_cndmask_b32_e32 v152, v166, v154, vcc
	v_cndmask_b32_e32 v153, v167, v155, vcc
	v_cndmask_b32_e64 v155, v185, v165, s[0:1]
	v_cndmask_b32_e64 v154, v183, v164, s[0:1]
	v_pk_fma_f32 v[154:155], v[140:141], v[154:155], v[144:145]
	v_lshlrev_b32_e32 v164, 16, v162
	v_and_b32_e32 v165, 0xffff0000, v162
	v_pk_fma_f32 v[154:155], v[136:137], v[176:177], v[154:155]
	v_cndmask_b32_e64 v153, v189, v153, s[0:1]
	v_pk_fma_f32 v[154:155], v[132:133], v[164:165], v[154:155]
	v_cndmask_b32_e64 v152, v187, v152, s[0:1]
	v_pk_mul_f32 v[164:165], v[154:155], s[26:27] op_sel_hi:[1,0]
	v_pk_mul_f32 v[154:155], v[154:155], 0.5 op_sel_hi:[1,0]
	v_med3_f32 v164, v164, s71, v224
	v_med3_f32 v165, v165, s71, v224
	v_pk_mul_f32 v[166:167], v[164:165], v[164:165]
	v_pk_fma_f32 v[152:153], v[142:143], v[152:153], v[146:147]
	v_pk_fma_f32 v[176:177], v[166:167], s[28:29], v[148:149] op_sel_hi:[1,0,0] neg_lo:[1,0,0] neg_hi:[1,0,0]
	v_pk_fma_f32 v[152:153], v[138:139], v[178:179], v[152:153]
	v_pk_fma_f32 v[176:177], v[166:167], v[176:177], s[34:35] op_sel_hi:[1,1,0]
	s_nop 0
	v_pk_fma_f32 v[176:177], v[166:167], v[176:177], s[36:37] op_sel_hi:[1,1,0]
	s_nop 0
	v_pk_fma_f32 v[176:177], v[166:167], v[176:177], s[38:39] op_sel_hi:[1,1,0]
	s_nop 0
	v_pk_fma_f32 v[176:177], v[166:167], v[176:177], s[40:41] op_sel_hi:[1,1,0]
	s_nop 0
	v_pk_fma_f32 v[176:177], v[166:167], v[176:177], s[42:43] op_sel_hi:[1,1,0]
	s_nop 0
	v_pk_fma_f32 v[166:167], v[166:167], v[176:177], s[44:45] op_sel_hi:[1,1,0]
	s_nop 0
	v_pk_mul_f32 v[164:165], v[164:165], v[166:167]
	s_nop 0
	v_pk_fma_f32 v[154:155], v[154:155], v[164:165], v[154:155]
	s_nop 0
	v_mul_f32_e32 v154, v44, v154
	v_mul_f32_e32 v166, v184, v154
	v_mul_f32_e32 v154, v45, v155
	v_mul_f32_e32 v167, v184, v154
	v_lshlrev_b32_e32 v154, 16, v163
	v_and_b32_e32 v155, 0xffff0000, v163
	v_pk_fma_f32 v[152:153], v[134:135], v[154:155], v[152:153]
	s_nop 0
	v_pk_mul_f32 v[154:155], v[152:153], s[26:27] op_sel_hi:[1,0]
	v_pk_mul_f32 v[152:153], v[152:153], 0.5 op_sel_hi:[1,0]
	v_med3_f32 v154, v154, s71, v224
	v_med3_f32 v155, v155, s71, v224
	v_pk_mul_f32 v[162:163], v[154:155], v[154:155]
	s_nop 0
	v_pk_fma_f32 v[164:165], v[162:163], s[28:29], v[148:149] op_sel_hi:[1,0,0] neg_lo:[1,0,0] neg_hi:[1,0,0]
	s_nop 0
	v_pk_fma_f32 v[164:165], v[162:163], v[164:165], s[34:35] op_sel_hi:[1,1,0]
	s_nop 0
	v_pk_fma_f32 v[164:165], v[162:163], v[164:165], s[36:37] op_sel_hi:[1,1,0]
	s_nop 0
	v_pk_fma_f32 v[164:165], v[162:163], v[164:165], s[38:39] op_sel_hi:[1,1,0]
	s_nop 0
	v_pk_fma_f32 v[164:165], v[162:163], v[164:165], s[40:41] op_sel_hi:[1,1,0]
	s_nop 0
	v_pk_fma_f32 v[164:165], v[162:163], v[164:165], s[42:43] op_sel_hi:[1,1,0]
	s_nop 0
	v_pk_fma_f32 v[162:163], v[162:163], v[164:165], s[44:45] op_sel_hi:[1,1,0]
	s_nop 0
	v_pk_mul_f32 v[154:155], v[154:155], v[162:163]
	s_nop 0
	v_pk_fma_f32 v[152:153], v[152:153], v[154:155], v[152:153]
	v_mov_b32_dpp v155, v151 row_ror:2 row_mask:0xf bank_mask:0xf bound_ctrl:1
	v_mul_f32_e32 v152, v46, v152
	v_mul_f32_e32 v154, v184, v152
	v_mul_f32_e32 v152, v47, v153
	v_mul_f32_e32 v153, v184, v152
	v_cvt_pk_bf16_f32 v152, v166, v167
	v_cvt_pk_bf16_f32 v153, v154, v153
	global_store_dwordx2 v[156:157], v[152:153], off sc1
	v_mov_b32_dpp v154, v150 row_ror:2 row_mask:0xf bank_mask:0xf bound_ctrl:1
	v_mov_b32_dpp v153, v151 row_ror:1 row_mask:0xf bank_mask:0xf bound_ctrl:1
	v_mov_b32_dpp v152, v150 row_ror:1 row_mask:0xf bank_mask:0xf bound_ctrl:1
	v_mov_b32_dpp v154, v150 row_shr:2 row_mask:0xf bank_mask:0xf
	v_mov_b32_dpp v153, v151 row_shr:1 row_mask:0xf bank_mask:0xf
	v_mov_b32_dpp v155, v151 row_shr:2 row_mask:0xf bank_mask:0xf
	v_and_b32_e32 v162, 0xffff0000, v153
	v_mov_b32_dpp v152, v150 row_shr:1 row_mask:0xf bank_mask:0xf
	v_lshlrev_b32_e32 v164, 16, v154
	v_and_b32_e32 v163, 0xffff0000, v154
	v_lshlrev_b32_e32 v165, 16, v155
	v_and_b32_e32 v166, 0xffff0000, v155
	s_waitcnt vmcnt(1)
; __device__ __forceinline__ unsigned cvt_pk_bf16(float lo, float hi) { unsigned r; asm volatile("v_cvt_pk_bf16_f32 %0, %1, %2" : "=v"(r) : "v"(lo), "v"(hi)); return r; }
;     static __device__ __forceinline__ void unpk4(const u32x2 w, float (&o)[4]) { o[0] = bf_lo(w.x); o[1] = bf_hi(w.x); o[2] = bf_lo(w.y); o[3] = bf_hi(w.y); }
;     template <int N> static __device__ __forceinline__ u32x2 dpp_prev(const u32x2 pv, const u32x2 cur) { u32x2 r; r.x = dpp_prev1<N>(pv.x, cur.x); r.y = dpp_prev1<N>(pv.y, cur.y); return r; }
;     static __device__ __forceinline__ void finish(const float (&g0)[4], const float (&g1)[4], const float (&g2)[4], const float (&w0)[4], const float (&w1)[4], const float (&w2)[4], const float (&bb)[4],
;                                                   const f32x4 v, float rs, bf16_t* dst) {
;         float h[4];
; #pragma unroll
;         for (int j = 0; j < 4; j += 2) {
;             const f32x2 gc = (f32x2){bb[j] + w0[j] * g2[j] + w1[j] * g1[j] + w2[j] * g0[j], bb[j + 1] + w0[j + 1] * g2[j + 1] + w1[j + 1] * g1[j + 1] + w2[j + 1] * g0[j + 1]};
;             const f32x2 ge = gelu_pk(gc); h[j] = ge.x * v[j] * rs; h[j + 1] = ge.y * v[j + 1] * rs; }
;         u32x2 w; w.x = cvt_pk_bf16(h[0], h[1]); w.y = cvt_pk_bf16(h[2], h[3]);
;         *(u32x2*)dst = w;
;     __device__ __forceinline__ void operator()(const f32x4 (&acc)[2][2][4][2], const Unit& u, int wr, int wc, int fr, int fq) const {
;     ...
;                 for (int m = mh; m < mh + 2; ++m) { const int row = row0 + m * 16; const float* cx = ctx + (size_t)((row - 32768) >> 3) * 2 * 2816 + col;
;                     c0[m] = *(const f32x4*)cx; c1[m] = *(const f32x4*)(cx + 2816); }
; #pragma unroll
;                 for (int m = mh; m < mh + 2; ++m) { const int row = row0 + m * 16; const u32x2 cur = gq[m];
;                     const u32x2 q1 = dpp_prev<1>(cur, cur), q2 = dpp_prev<2>(cur, cur);
;                     float g0[4], g1[4], g2[4]; unpk4(cur, g0); unpk4(q1, g1); unpk4(q2, g2);
; #pragma unroll
;                     for (int j = 0; j < 4; ++j) { const float x1 = c1[m][j], x0 = c0[m][j];
;                         if (i < 1) g1[j] = x1;
;                         if (i < 2) g2[j] = (i == 1) ? x1 : x0; }
;                     finish(g0, g1, g2, w0, w1, w2, bb, acc[0][bj][m][hv], rs8[0][m], H + (size_t)row * 2816 + col); }
	v_cndmask_b32_e64 v155, v162, v175, s[6:7]
	v_cndmask_b32_e32 v162, v168, v172, vcc
	v_cndmask_b32_e32 v167, v169, v173, vcc
	v_lshlrev_b32_e32 v156, 16, v152
	v_and_b32_e32 v152, 0xffff0000, v152
	v_cndmask_b32_e64 v163, v163, v167, s[0:1]
	v_cndmask_b32_e64 v162, v164, v162, s[0:1]
	v_lshlrev_b32_e32 v157, 16, v153
	v_cndmask_b32_e64 v153, v152, v173, s[6:7]
	v_cndmask_b32_e64 v152, v156, v172, s[6:7]
	v_pk_fma_f32 v[140:141], v[140:141], v[162:163], v[144:145]
	v_cndmask_b32_e64 v154, v157, v174, s[6:7]
	v_pk_fma_f32 v[136:137], v[136:137], v[152:153], v[140:141]
	v_cndmask_b32_e32 v156, v170, v174, vcc
	v_pk_fma_f32 v[132:133], v[132:133], v[160:161], v[136:137]
	v_cndmask_b32_e32 v157, v171, v175, vcc
	v_pk_mul_f32 v[136:137], v[132:133], s[26:27] op_sel_hi:[1,0]
	v_cndmask_b32_e64 v157, v166, v157, s[0:1]
	v_cndmask_b32_e64 v156, v165, v156, s[0:1]
	v_med3_f32 v136, v136, s71, v224
	v_med3_f32 v137, v137, s71, v224
	v_pk_fma_f32 v[142:143], v[142:143], v[156:157], v[146:147]
	v_pk_mul_f32 v[140:141], v[136:137], v[136:137]
	v_pk_fma_f32 v[138:139], v[138:139], v[154:155], v[142:143]
	v_pk_fma_f32 v[142:143], v[140:141], s[28:29], v[148:149] op_sel_hi:[1,0,0] neg_lo:[1,0,0] neg_hi:[1,0,0]
	v_pk_mul_f32 v[132:133], v[132:133], 0.5 op_sel_hi:[1,0]
	v_pk_fma_f32 v[142:143], v[140:141], v[142:143], s[34:35] op_sel_hi:[1,1,0]
	s_nop 0
	v_pk_fma_f32 v[142:143], v[140:141], v[142:143], s[36:37] op_sel_hi:[1,1,0]
	s_nop 0
	v_pk_fma_f32 v[142:143], v[140:141], v[142:143], s[38:39] op_sel_hi:[1,1,0]
	s_nop 0
	v_pk_fma_f32 v[142:143], v[140:141], v[142:143], s[40:41] op_sel_hi:[1,1,0]
	s_nop 0
	v_pk_fma_f32 v[142:143], v[140:141], v[142:143], s[42:43] op_sel_hi:[1,1,0]
	s_nop 0
	v_pk_fma_f32 v[140:141], v[140:141], v[142:143], s[44:45] op_sel_hi:[1,1,0]
	s_nop 0
	v_pk_mul_f32 v[136:137], v[136:137], v[140:141]
	s_nop 0
	v_pk_fma_f32 v[132:133], v[132:133], v[136:137], v[132:133]
	s_nop 0
	v_mul_f32_e32 v132, v36, v132
	v_mul_f32_e32 v140, v2, v132
	v_mul_f32_e32 v132, v37, v133
	v_mul_f32_e32 v141, v2, v132
	v_lshlrev_b32_e32 v132, 16, v151
	v_and_b32_e32 v133, 0xffff0000, v151
	v_pk_fma_f32 v[132:133], v[134:135], v[132:133], v[138:139]
	s_nop 0
	v_pk_mul_f32 v[134:135], v[132:133], s[26:27] op_sel_hi:[1,0]
	v_pk_mul_f32 v[132:133], v[132:133], 0.5 op_sel_hi:[1,0]
	v_med3_f32 v134, v134, s71, v224
	v_med3_f32 v135, v135, s71, v224
	v_pk_mul_f32 v[136:137], v[134:135], v[134:135]
	s_nop 0
	v_pk_fma_f32 v[138:139], v[136:137], s[28:29], v[148:149] op_sel_hi:[1,0,0] neg_lo:[1,0,0] neg_hi:[1,0,0]
	s_nop 0
	v_pk_fma_f32 v[138:139], v[136:137], v[138:139], s[34:35] op_sel_hi:[1,1,0]
	s_nop 0
	v_pk_fma_f32 v[138:139], v[136:137], v[138:139], s[36:37] op_sel_hi:[1,1,0]
	s_nop 0
	v_pk_fma_f32 v[138:139], v[136:137], v[138:139], s[38:39] op_sel_hi:[1,1,0]
	s_nop 0
	v_pk_fma_f32 v[138:139], v[136:137], v[138:139], s[40:41] op_sel_hi:[1,1,0]
	s_nop 0
	v_pk_fma_f32 v[138:139], v[136:137], v[138:139], s[42:43] op_sel_hi:[1,1,0]
	s_nop 0
	v_pk_fma_f32 v[136:137], v[136:137], v[138:139], s[44:45] op_sel_hi:[1,1,0]
	s_nop 0
	v_pk_mul_f32 v[134:135], v[134:135], v[136:137]
	s_nop 0
	v_pk_fma_f32 v[132:133], v[132:133], v[134:135], v[132:133]
	s_nop 0
	v_mul_f32_e32 v132, v38, v132
	v_mul_f32_e32 v134, v2, v132
	v_mul_f32_e32 v132, v39, v133
	v_mul_f32_e32 v133, v2, v132
	v_cvt_pk_bf16_f32 v132, v140, v141
	v_cvt_pk_bf16_f32 v133, v134, v133
	global_store_dwordx2 v[158:159], v[132:133], off sc1
	s_cbranch_execz .LBB0_3142

; __device__ __forceinline__ unsigned cvt_pk_bf16(float lo, float hi) { unsigned r; asm volatile("v_cvt_pk_bf16_f32 %0, %1, %2" : "=v"(r) : "v"(lo), "v"(hi)); return r; }
;     static __device__ __forceinline__ void unpk4(const u32x2 w, float (&o)[4]) { o[0] = bf_lo(w.x); o[1] = bf_hi(w.x); o[2] = bf_lo(w.y); o[3] = bf_hi(w.y); }
;     template <int N> static __device__ __forceinline__ u32x2 dpp_prev(const u32x2 pv, const u32x2 cur) { u32x2 r; r.x = dpp_prev1<N>(pv.x, cur.x); r.y = dpp_prev1<N>(pv.y, cur.y); return r; }
;     static __device__ __forceinline__ u32x2 finish2(const float (&g0)[4], const float (&g1)[4], const float (&g2)[4], const float (&w0)[4], const float (&w1)[4], const float (&w2)[4], const float (&bb)[4],
;                                                     const f32x4 v, float rs) {
;         float h[4];
; #pragma unroll
;         for (int j = 0; j < 4; j += 2) {
;             const f32x2 gc = (f32x2){bb[j] + w0[j] * g2[j] + w1[j] * g1[j] + w2[j] * g0[j], bb[j + 1] + w0[j + 1] * g2[j + 1] + w1[j + 1] * g1[j + 1] + w2[j + 1] * g0[j + 1]};
;             const f32x2 ge = gelu_pk(gc) * ((f32x2){v[j], v[j + 1]} * rs); h[j] = ge.x; h[j + 1] = ge.y; }
;         u32x2 w; w.x = cvt_pk_bf16(h[0], h[1]); w.y = cvt_pk_bf16(h[2], h[3]); return w;
;     __device__ __forceinline__ void operator()(const f32x4 (&acc)[2][2][4][2], const Unit& u, int wr, int wc, int fr, int fq) const {
;     ...
;                 for (int m = 0; m < 4; ++m) { const u32x4 cur = gq[m]; u32x4 hw;
; #pragma unroll
;                     for (int hv = 0; hv < 2; ++hv) { const u32x2 c2 = half2(cur, hv), p2 = half2(pv, hv);
;                         const u32x2 q1 = dpp_prev<1>(p2, c2), q2 = dpp_prev<2>(p2, c2);
;                         float g0[4], g1[4], g2[4]; unpk4(c2, g0); unpk4(q1, g1); unpk4(q2, g2);
;                         const u32x2 r = finish2(g0, g1, g2, w0[hv], w1[hv], w2[hv], bb[hv], acc[ai][bj][m][hv], rs8[ai][m]);
;                         if (hv == 0) { hw.x = r.x; hw.y = r.y; } else { hw.z = r.x; hw.w = r.y; } }
;                     *(u32x4*)(H + (size_t)(R0 + fr + 16 * m) * 2816 + col8) = hw;
.LBB0_3145:
	s_waitcnt vmcnt(0)
	v_mov_b32_dpp v195, v180 row_ror:2 row_mask:0xf bank_mask:0xf bound_ctrl:1
	v_mov_b32_dpp v191, v180 row_ror:1 row_mask:0xf bank_mask:0xf bound_ctrl:1
	v_mad_i64_i32 v[230:231], s[0:1], v210, s67, 0
	v_mov_b32_dpp v195, v176 row_shr:2 row_mask:0xf bank_mask:0xf
	v_mov_b32_dpp v191, v176 row_shr:1 row_mask:0xf bank_mask:0xf
	v_lshlrev_b32_e32 v210, 16, v195
	v_and_b32_e32 v211, 0xffff0000, v195
	v_mov_b32_dpp v193, v181 row_ror:1 row_mask:0xf bank_mask:0xf bound_ctrl:1
	v_mov_b32_dpp v225, v181 row_ror:2 row_mask:0xf bank_mask:0xf bound_ctrl:1
	v_lshlrev_b32_e32 v180, 16, v191
	v_and_b32_e32 v181, 0xffff0000, v191
	v_pk_fma_f32 v[210:211], v[148:149], v[210:211], v[160:161]
	v_lshlrev_b32_e32 v232, 16, v176
	v_and_b32_e32 v233, 0xffff0000, v176
	v_pk_fma_f32 v[180:181], v[152:153], v[180:181], v[210:211]
	v_mov_b32_dpp v225, v177 row_shr:2 row_mask:0xf bank_mask:0xf
	v_pk_fma_f32 v[180:181], v[156:157], v[232:233], v[180:181]
	v_mov_b32_dpp v193, v177 row_shr:1 row_mask:0xf bank_mask:0xf
	v_pk_mul_f32 v[210:211], v[180:181], s[26:27] op_sel_hi:[1,0]
	v_lshlrev_b32_e32 v228, 16, v225
	v_med3_f32 v232, v210, s71, v224
	v_med3_f32 v233, v211, s71, v224
	v_pk_mul_f32 v[234:235], v[232:233], v[232:233]
	v_mov_b64_e32 v[210:211], s[30:31]
	v_pk_fma_f32 v[236:237], v[234:235], s[28:29], v[210:211] op_sel_hi:[1,0,0] neg_lo:[1,0,0] neg_hi:[1,0,0]
	v_and_b32_e32 v229, 0xffff0000, v225
	v_pk_fma_f32 v[236:237], v[234:235], v[236:237], s[34:35] op_sel_hi:[1,1,0]
	v_pk_mul_f32 v[180:181], v[180:181], 0.5 op_sel_hi:[1,0]
	v_pk_fma_f32 v[236:237], v[234:235], v[236:237], s[36:37] op_sel_hi:[1,1,0]
	v_lshlrev_b32_e32 v226, 16, v193
	v_pk_fma_f32 v[236:237], v[234:235], v[236:237], s[38:39] op_sel_hi:[1,1,0]
	v_and_b32_e32 v227, 0xffff0000, v193
	v_pk_fma_f32 v[236:237], v[234:235], v[236:237], s[40:41] op_sel_hi:[1,1,0]
	v_pk_mul_f32 v[128:129], v[128:129], v[188:189] op_sel_hi:[1,0]
	v_pk_fma_f32 v[236:237], v[234:235], v[236:237], s[42:43] op_sel_hi:[1,1,0]
	v_pk_fma_f32 v[228:229], v[150:151], v[228:229], v[162:163]
	v_pk_fma_f32 v[234:235], v[234:235], v[236:237], s[44:45] op_sel_hi:[1,1,0]
	v_pk_fma_f32 v[226:227], v[154:155], v[226:227], v[228:229]
	v_pk_mul_f32 v[232:233], v[232:233], v[234:235]
	v_pk_mul_f32 v[130:131], v[130:131], v[188:189] op_sel_hi:[1,0]
	v_pk_fma_f32 v[180:181], v[180:181], v[232:233], v[180:181]
	v_pk_mul_f32 v[124:125], v[124:125], v[188:189] op_sel_hi:[1,0]
	v_pk_mul_f32 v[128:129], v[128:129], v[180:181]
	v_lshlrev_b32_e32 v180, 16, v177
	v_and_b32_e32 v181, 0xffff0000, v177
	v_pk_fma_f32 v[180:181], v[158:159], v[180:181], v[226:227]
	v_readlane_b32 s0, v240, 58
	v_pk_mul_f32 v[226:227], v[180:181], s[26:27] op_sel_hi:[1,0]
	v_pk_mul_f32 v[180:181], v[180:181], 0.5 op_sel_hi:[1,0]
	v_med3_f32 v226, v226, s71, v224
	v_med3_f32 v227, v227, s71, v224
	v_pk_mul_f32 v[228:229], v[226:227], v[226:227]
	v_readlane_b32 s1, v240, 59
	v_pk_fma_f32 v[232:233], v[228:229], s[28:29], v[210:211] op_sel_hi:[1,0,0] neg_lo:[1,0,0] neg_hi:[1,0,0]
	v_pk_mul_f32 v[126:127], v[126:127], v[188:189] op_sel_hi:[1,0]
	v_pk_fma_f32 v[232:233], v[228:229], v[232:233], s[34:35] op_sel_hi:[1,1,0]
	v_pk_mul_f32 v[120:121], v[120:121], v[186:187] op_sel_hi:[1,0]
	v_pk_fma_f32 v[232:233], v[228:229], v[232:233], s[36:37] op_sel_hi:[1,1,0]
	v_pk_mul_f32 v[122:123], v[122:123], v[186:187] op_sel_hi:[1,0]
	v_pk_fma_f32 v[232:233], v[228:229], v[232:233], s[38:39] op_sel_hi:[1,1,0]
	v_pk_mul_f32 v[116:117], v[116:117], v[186:187] op_sel_hi:[1,0]
	v_pk_fma_f32 v[232:233], v[228:229], v[232:233], s[40:41] op_sel_hi:[1,1,0]
	v_pk_mul_f32 v[118:119], v[118:119], v[186:187] op_sel_hi:[1,0]
	v_pk_fma_f32 v[232:233], v[228:229], v[232:233], s[42:43] op_sel_hi:[1,1,0]
	v_pk_mul_f32 v[112:113], v[112:113], v[184:185] op_sel_hi:[1,0]
	v_pk_fma_f32 v[228:229], v[228:229], v[232:233], s[44:45] op_sel_hi:[1,1,0]
	v_pk_mul_f32 v[114:115], v[114:115], v[184:185] op_sel_hi:[1,0]
	v_pk_mul_f32 v[226:227], v[226:227], v[228:229]
	v_lshlrev_b32_e32 v228, 16, v178
	v_pk_fma_f32 v[180:181], v[180:181], v[226:227], v[180:181]
	v_cvt_pk_bf16_f32 v226, v128, v129
	v_mov_b32_dpp v129, v182 row_ror:1 row_mask:0xf bank_mask:0xf bound_ctrl:1
	v_pk_mul_f32 v[130:131], v[130:131], v[180:181]
	v_mov_b32_dpp v181, v182 row_ror:2 row_mask:0xf bank_mask:0xf bound_ctrl:1
	v_mov_b32_dpp v129, v178 row_shr:1 row_mask:0xf bank_mask:0xf
	v_lshlrev_b32_e32 v128, 16, v129
	v_mov_b32_dpp v181, v178 row_shr:2 row_mask:0xf bank_mask:0xf
	v_lshlrev_b32_e32 v180, 16, v181
	v_and_b32_e32 v181, 0xffff0000, v181
	v_and_b32_e32 v129, 0xffff0000, v129
	v_pk_fma_f32 v[180:181], v[132:133], v[180:181], v[144:145]
	v_and_b32_e32 v229, 0xffff0000, v178
	v_pk_fma_f32 v[128:129], v[136:137], v[128:129], v[180:181]
	v_cvt_pk_bf16_f32 v227, v130, v131
	v_mov_b32_dpp v131, v183 row_ror:1 row_mask:0xf bank_mask:0xf bound_ctrl:1
	v_pk_fma_f32 v[128:129], v[140:141], v[228:229], v[128:129]
	v_mov_b32_dpp v183, v183 row_ror:2 row_mask:0xf bank_mask:0xf bound_ctrl:1
	v_pk_mul_f32 v[180:181], v[128:129], s[26:27] op_sel_hi:[1,0]
	v_mov_b32_dpp v131, v179 row_shr:1 row_mask:0xf bank_mask:0xf
	v_med3_f32 v180, v180, s71, v224
	v_med3_f32 v181, v181, s71, v224
	v_pk_mul_f32 v[228:229], v[180:181], v[180:181]
	v_mov_b32_dpp v183, v179 row_shr:2 row_mask:0xf bank_mask:0xf
	v_pk_fma_f32 v[232:233], v[228:229], s[28:29], v[210:211] op_sel_hi:[1,0,0] neg_lo:[1,0,0] neg_hi:[1,0,0]
	v_lshlrev_b32_e32 v182, 16, v183
	v_pk_fma_f32 v[232:233], v[228:229], v[232:233], s[34:35] op_sel_hi:[1,1,0]
	v_and_b32_e32 v183, 0xffff0000, v183
	v_pk_fma_f32 v[232:233], v[228:229], v[232:233], s[36:37] op_sel_hi:[1,1,0]
; __device__ __forceinline__ unsigned cvt_pk_bf16(float lo, float hi) { unsigned r; asm volatile("v_cvt_pk_bf16_f32 %0, %1, %2" : "=v"(r) : "v"(lo), "v"(hi)); return r; }
;     static __device__ __forceinline__ void unpk4(const u32x2 w, float (&o)[4]) { o[0] = bf_lo(w.x); o[1] = bf_hi(w.x); o[2] = bf_lo(w.y); o[3] = bf_hi(w.y); }
;     template <int N> static __device__ __forceinline__ u32x2 dpp_prev(const u32x2 pv, const u32x2 cur) { u32x2 r; r.x = dpp_prev1<N>(pv.x, cur.x); r.y = dpp_prev1<N>(pv.y, cur.y); return r; }
;     static __device__ __forceinline__ u32x2 finish2(const float (&g0)[4], const float (&g1)[4], const float (&g2)[4], const float (&w0)[4], const float (&w1)[4], const float (&w2)[4], const float (&bb)[4],
;                                                     const f32x4 v, float rs) {
;         float h[4];
; #pragma unroll
;         for (int j = 0; j < 4; j += 2) {
;             const f32x2 gc = (f32x2){bb[j] + w0[j] * g2[j] + w1[j] * g1[j] + w2[j] * g0[j], bb[j + 1] + w0[j + 1] * g2[j + 1] + w1[j + 1] * g1[j + 1] + w2[j + 1] * g0[j + 1]};
;             const f32x2 ge = gelu_pk(gc) * ((f32x2){v[j], v[j + 1]} * rs); h[j] = ge.x; h[j + 1] = ge.y; }
;         u32x2 w; w.x = cvt_pk_bf16(h[0], h[1]); w.y = cvt_pk_bf16(h[2], h[3]); return w;
;     __device__ __forceinline__ void operator()(const f32x4 (&acc)[2][2][4][2], const Unit& u, int wr, int wc, int fr, int fq) const {
;     ...
;                 for (int m = 0; m < 4; ++m) { const u32x4 cur = gq[m]; u32x4 hw;
; #pragma unroll
;                     for (int hv = 0; hv < 2; ++hv) { const u32x2 c2 = half2(cur, hv), p2 = half2(pv, hv);
;                         const u32x2 q1 = dpp_prev<1>(p2, c2), q2 = dpp_prev<2>(p2, c2);
;                         float g0[4], g1[4], g2[4]; unpk4(c2, g0); unpk4(q1, g1); unpk4(q2, g2);
;                         const u32x2 r = finish2(g0, g1, g2, w0[hv], w1[hv], w2[hv], bb[hv], acc[ai][bj][m][hv], rs8[ai][m]);
;                         if (hv == 0) { hw.x = r.x; hw.y = r.y; } else { hw.z = r.x; hw.w = r.y; } }
;                     *(u32x4*)(H + (size_t)(R0 + fr + 16 * m) * 2816 + col8) = hw;
	v_pk_mul_f32 v[128:129], v[128:129], 0.5 op_sel_hi:[1,0]
	v_pk_fma_f32 v[232:233], v[228:229], v[232:233], s[38:39] op_sel_hi:[1,1,0]
	v_lshlrev_b32_e32 v130, 16, v131
	v_pk_fma_f32 v[232:233], v[228:229], v[232:233], s[40:41] op_sel_hi:[1,1,0]
	v_and_b32_e32 v131, 0xffff0000, v131
	v_pk_fma_f32 v[232:233], v[228:229], v[232:233], s[42:43] op_sel_hi:[1,1,0]
	v_pk_mul_f32 v[108:109], v[108:109], v[184:185] op_sel_hi:[1,0]
	v_pk_fma_f32 v[228:229], v[228:229], v[232:233], s[44:45] op_sel_hi:[1,1,0]
	v_pk_mul_f32 v[110:111], v[110:111], v[184:185] op_sel_hi:[1,0]
	v_pk_mul_f32 v[180:181], v[180:181], v[228:229]
	v_pk_mul_f32 v[104:105], v[104:105], v[2:3] op_sel_hi:[1,0]
	v_pk_fma_f32 v[128:129], v[128:129], v[180:181], v[128:129]
	v_pk_fma_f32 v[180:181], v[134:135], v[182:183], v[146:147]
	v_pk_mul_f32 v[124:125], v[124:125], v[128:129]
	v_lshlrev_b32_e32 v128, 16, v179
	v_and_b32_e32 v129, 0xffff0000, v179
	v_pk_fma_f32 v[130:131], v[138:139], v[130:131], v[180:181]
	v_cvt_pk_bf16_f32 v228, v124, v125
	v_pk_mul_f32 v[106:107], v[106:107], v[2:3] op_sel_hi:[1,0]
	v_pk_fma_f32 v[128:129], v[142:143], v[128:129], v[130:131]
	v_pk_mul_f32 v[100:101], v[100:101], v[2:3] op_sel_hi:[1,0]
	v_pk_mul_f32 v[130:131], v[128:129], s[26:27] op_sel_hi:[1,0]
	v_pk_mul_f32 v[128:129], v[128:129], 0.5 op_sel_hi:[1,0]
	v_med3_f32 v130, v130, s71, v224
	v_med3_f32 v131, v131, s71, v224
	v_pk_mul_f32 v[180:181], v[130:131], v[130:131]
	s_addk_i32 s47, 0x80
	v_pk_fma_f32 v[182:183], v[180:181], s[28:29], v[210:211] op_sel_hi:[1,0,0] neg_lo:[1,0,0] neg_hi:[1,0,0]
	v_add_u32_e32 v1, s47, v1
	v_pk_fma_f32 v[182:183], v[180:181], v[182:183], s[34:35] op_sel_hi:[1,1,0]
	v_pk_mul_f32 v[102:103], v[102:103], v[2:3] op_sel_hi:[1,0]
	v_pk_fma_f32 v[182:183], v[180:181], v[182:183], s[36:37] op_sel_hi:[1,1,0]
	s_nop 0
	v_pk_fma_f32 v[182:183], v[180:181], v[182:183], s[38:39] op_sel_hi:[1,1,0]
	s_nop 0
	v_pk_fma_f32 v[182:183], v[180:181], v[182:183], s[40:41] op_sel_hi:[1,1,0]
	s_nop 0
	v_pk_fma_f32 v[182:183], v[180:181], v[182:183], s[42:43] op_sel_hi:[1,1,0]
	s_nop 0
	v_pk_fma_f32 v[180:181], v[180:181], v[182:183], s[44:45] op_sel_hi:[1,1,0]
	v_lshlrev_b32_e32 v182, 16, v172
	v_pk_mul_f32 v[130:131], v[130:131], v[180:181]
	v_lshlrev_b64 v[180:181], 1, v[212:213]
	v_pk_fma_f32 v[128:129], v[128:129], v[130:131], v[128:129]
	v_lshl_add_u64 v[130:131], s[0:1], 0, v[230:231]
	v_pk_mul_f32 v[126:127], v[126:127], v[128:129]
	v_lshl_add_u64 v[124:125], v[130:131], 0, v[180:181]
	v_mov_b32_dpp v129, v176 row_ror:2 row_mask:0xf bank_mask:0xf bound_ctrl:1
	v_cvt_pk_bf16_f32 v229, v126, v127
	global_store_dwordx4 v[124:125], v[226:229], off sc1
	v_mov_b32_dpp v125, v176 row_ror:1 row_mask:0xf bank_mask:0xf bound_ctrl:1
	v_mov_b32_dpp v129, v172 row_shr:2 row_mask:0xf bank_mask:0xf
	v_lshlrev_b32_e32 v128, 16, v129
	v_mov_b32_dpp v125, v172 row_shr:1 row_mask:0xf bank_mask:0xf
	v_and_b32_e32 v129, 0xffff0000, v129
	v_lshlrev_b32_e32 v124, 16, v125
	v_and_b32_e32 v125, 0xffff0000, v125
	v_pk_fma_f32 v[128:129], v[148:149], v[128:129], v[160:161]
	v_and_b32_e32 v183, 0xffff0000, v172
	v_pk_fma_f32 v[124:125], v[152:153], v[124:125], v[128:129]
	v_mov_b32_dpp v127, v177 row_ror:1 row_mask:0xf bank_mask:0xf bound_ctrl:1
	v_pk_fma_f32 v[124:125], v[156:157], v[182:183], v[124:125]
	v_mov_b32_dpp v177, v177 row_ror:2 row_mask:0xf bank_mask:0xf bound_ctrl:1
	v_pk_mul_f32 v[128:129], v[124:125], s[26:27] op_sel_hi:[1,0]
	v_mov_b32_dpp v127, v173 row_shr:1 row_mask:0xf bank_mask:0xf
	v_med3_f32 v128, v128, s71, v224
	v_med3_f32 v129, v129, s71, v224
	v_pk_mul_f32 v[182:183], v[128:129], v[128:129]
	v_mov_b32_dpp v177, v173 row_shr:2 row_mask:0xf bank_mask:0xf
	v_pk_fma_f32 v[226:227], v[182:183], s[28:29], v[210:211] op_sel_hi:[1,0,0] neg_lo:[1,0,0] neg_hi:[1,0,0]
	v_lshlrev_b32_e32 v176, 16, v177
	v_pk_fma_f32 v[226:227], v[182:183], v[226:227], s[34:35] op_sel_hi:[1,1,0]
	v_and_b32_e32 v177, 0xffff0000, v177
	v_pk_fma_f32 v[226:227], v[182:183], v[226:227], s[36:37] op_sel_hi:[1,1,0]
	v_pk_mul_f32 v[124:125], v[124:125], 0.5 op_sel_hi:[1,0]
	v_pk_fma_f32 v[226:227], v[182:183], v[226:227], s[38:39] op_sel_hi:[1,1,0]
	v_lshlrev_b32_e32 v126, 16, v127
	v_pk_fma_f32 v[226:227], v[182:183], v[226:227], s[40:41] op_sel_hi:[1,1,0]
	v_and_b32_e32 v127, 0xffff0000, v127
	v_pk_fma_f32 v[226:227], v[182:183], v[226:227], s[42:43] op_sel_hi:[1,1,0]
	s_nop 0
	v_pk_fma_f32 v[182:183], v[182:183], v[226:227], s[44:45] op_sel_hi:[1,1,0]
	s_nop 0
	v_pk_mul_f32 v[128:129], v[128:129], v[182:183]
	s_nop 0
	v_pk_fma_f32 v[124:125], v[124:125], v[128:129], v[124:125]
	v_pk_fma_f32 v[128:129], v[150:151], v[176:177], v[162:163]
	v_pk_mul_f32 v[120:121], v[120:121], v[124:125]
	v_lshlrev_b32_e32 v124, 16, v173
	v_and_b32_e32 v125, 0xffff0000, v173
	v_pk_fma_f32 v[126:127], v[154:155], v[126:127], v[128:129]
	v_cvt_pk_bf16_f32 v120, v120, v121
	s_nop 0
	v_pk_fma_f32 v[124:125], v[158:159], v[124:125], v[126:127]
	s_nop 0
	v_pk_mul_f32 v[126:127], v[124:125], s[26:27] op_sel_hi:[1,0]
	v_pk_mul_f32 v[124:125], v[124:125], 0.5 op_sel_hi:[1,0]
	v_med3_f32 v126, v126, s71, v224
	v_med3_f32 v127, v127, s71, v224
	v_pk_mul_f32 v[128:129], v[126:127], v[126:127]
	s_nop 0
	v_pk_fma_f32 v[176:177], v[128:129], s[28:29], v[210:211] op_sel_hi:[1,0,0] neg_lo:[1,0,0] neg_hi:[1,0,0]
	s_nop 0
	v_pk_fma_f32 v[176:177], v[128:129], v[176:177], s[34:35] op_sel_hi:[1,1,0]
	s_nop 0
	v_pk_fma_f32 v[176:177], v[128:129], v[176:177], s[36:37] op_sel_hi:[1,1,0]
	s_nop 0
	v_pk_fma_f32 v[176:177], v[128:129], v[176:177], s[38:39] op_sel_hi:[1,1,0]
	s_nop 0
	v_pk_fma_f32 v[176:177], v[128:129], v[176:177], s[40:41] op_sel_hi:[1,1,0]
; __device__ __forceinline__ unsigned cvt_pk_bf16(float lo, float hi) { unsigned r; asm volatile("v_cvt_pk_bf16_f32 %0, %1, %2" : "=v"(r) : "v"(lo), "v"(hi)); return r; }
;     static __device__ __forceinline__ void unpk4(const u32x2 w, float (&o)[4]) { o[0] = bf_lo(w.x); o[1] = bf_hi(w.x); o[2] = bf_lo(w.y); o[3] = bf_hi(w.y); }
;     template <int N> static __device__ __forceinline__ u32x2 dpp_prev(const u32x2 pv, const u32x2 cur) { u32x2 r; r.x = dpp_prev1<N>(pv.x, cur.x); r.y = dpp_prev1<N>(pv.y, cur.y); return r; }
;     static __device__ __forceinline__ u32x2 finish2(const float (&g0)[4], const float (&g1)[4], const float (&g2)[4], const float (&w0)[4], const float (&w1)[4], const float (&w2)[4], const float (&bb)[4],
;                                                     const f32x4 v, float rs) {
;         float h[4];
; #pragma unroll
;         for (int j = 0; j < 4; j += 2) {
;             const f32x2 gc = (f32x2){bb[j] + w0[j] * g2[j] + w1[j] * g1[j] + w2[j] * g0[j], bb[j + 1] + w0[j + 1] * g2[j + 1] + w1[j + 1] * g1[j + 1] + w2[j + 1] * g0[j + 1]};
;             const f32x2 ge = gelu_pk(gc) * ((f32x2){v[j], v[j + 1]} * rs); h[j] = ge.x; h[j + 1] = ge.y; }
;         u32x2 w; w.x = cvt_pk_bf16(h[0], h[1]); w.y = cvt_pk_bf16(h[2], h[3]); return w;
;     __device__ __forceinline__ void operator()(const f32x4 (&acc)[2][2][4][2], const Unit& u, int wr, int wc, int fr, int fq) const {
;     ...
;                 for (int m = 0; m < 4; ++m) { const u32x4 cur = gq[m]; u32x4 hw;
; #pragma unroll
;                     for (int hv = 0; hv < 2; ++hv) { const u32x2 c2 = half2(cur, hv), p2 = half2(pv, hv);
;                         const u32x2 q1 = dpp_prev<1>(p2, c2), q2 = dpp_prev<2>(p2, c2);
;                         float g0[4], g1[4], g2[4]; unpk4(c2, g0); unpk4(q1, g1); unpk4(q2, g2);
;                         const u32x2 r = finish2(g0, g1, g2, w0[hv], w1[hv], w2[hv], bb[hv], acc[ai][bj][m][hv], rs8[ai][m]);
;                         if (hv == 0) { hw.x = r.x; hw.y = r.y; } else { hw.z = r.x; hw.w = r.y; } }
;                     *(u32x4*)(H + (size_t)(R0 + fr + 16 * m) * 2816 + col8) = hw;
	s_nop 0
	v_pk_fma_f32 v[176:177], v[128:129], v[176:177], s[42:43] op_sel_hi:[1,1,0]
	s_nop 0
	v_pk_fma_f32 v[128:129], v[128:129], v[176:177], s[44:45] op_sel_hi:[1,1,0]
	v_lshlrev_b32_e32 v176, 16, v174
	v_pk_mul_f32 v[126:127], v[126:127], v[128:129]
	v_and_b32_e32 v177, 0xffff0000, v174
	v_pk_fma_f32 v[124:125], v[124:125], v[126:127], v[124:125]
	v_mov_b32_dpp v127, v178 row_ror:2 row_mask:0xf bank_mask:0xf bound_ctrl:1
	v_pk_mul_f32 v[122:123], v[122:123], v[124:125]
	v_mov_b32_dpp v125, v179 row_ror:1 row_mask:0xf bank_mask:0xf bound_ctrl:1
	v_cvt_pk_bf16_f32 v121, v122, v123
	v_mov_b32_dpp v127, v174 row_shr:2 row_mask:0xf bank_mask:0xf
	v_mov_b32_dpp v123, v178 row_ror:1 row_mask:0xf bank_mask:0xf bound_ctrl:1
	v_lshlrev_b32_e32 v126, 16, v127
	v_and_b32_e32 v127, 0xffff0000, v127
	v_mov_b32_dpp v123, v174 row_shr:1 row_mask:0xf bank_mask:0xf
	v_lshlrev_b32_e32 v122, 16, v123
	v_and_b32_e32 v123, 0xffff0000, v123
	v_pk_fma_f32 v[126:127], v[132:133], v[126:127], v[144:145]
	v_mov_b32_dpp v129, v179 row_ror:2 row_mask:0xf bank_mask:0xf bound_ctrl:1
	v_pk_fma_f32 v[122:123], v[136:137], v[122:123], v[126:127]
	v_mov_b32_dpp v125, v175 row_shr:1 row_mask:0xf bank_mask:0xf
	v_pk_fma_f32 v[122:123], v[140:141], v[176:177], v[122:123]
	v_mov_b32_dpp v129, v175 row_shr:2 row_mask:0xf bank_mask:0xf
	v_pk_mul_f32 v[126:127], v[122:123], s[26:27] op_sel_hi:[1,0]
	v_lshlrev_b32_e32 v128, 16, v129
	v_med3_f32 v126, v126, s71, v224
	v_med3_f32 v127, v127, s71, v224
	v_pk_mul_f32 v[176:177], v[126:127], v[126:127]
	v_and_b32_e32 v129, 0xffff0000, v129
	v_pk_fma_f32 v[178:179], v[176:177], s[28:29], v[210:211] op_sel_hi:[1,0,0] neg_lo:[1,0,0] neg_hi:[1,0,0]
	v_pk_mul_f32 v[122:123], v[122:123], 0.5 op_sel_hi:[1,0]
	v_pk_fma_f32 v[178:179], v[176:177], v[178:179], s[34:35] op_sel_hi:[1,1,0]
	v_lshlrev_b32_e32 v124, 16, v125
	v_pk_fma_f32 v[178:179], v[176:177], v[178:179], s[36:37] op_sel_hi:[1,1,0]
	v_and_b32_e32 v125, 0xffff0000, v125
	v_pk_fma_f32 v[178:179], v[176:177], v[178:179], s[38:39] op_sel_hi:[1,1,0]
	s_nop 0
	v_pk_fma_f32 v[178:179], v[176:177], v[178:179], s[40:41] op_sel_hi:[1,1,0]
	s_nop 0
	v_pk_fma_f32 v[178:179], v[176:177], v[178:179], s[42:43] op_sel_hi:[1,1,0]
	s_nop 0
	v_pk_fma_f32 v[176:177], v[176:177], v[178:179], s[44:45] op_sel_hi:[1,1,0]
	s_nop 0
	v_pk_mul_f32 v[126:127], v[126:127], v[176:177]
	s_nop 0
	v_pk_fma_f32 v[122:123], v[122:123], v[126:127], v[122:123]
	v_pk_fma_f32 v[126:127], v[134:135], v[128:129], v[146:147]
	v_pk_mul_f32 v[116:117], v[116:117], v[122:123]
	v_lshlrev_b32_e32 v122, 16, v175
	v_and_b32_e32 v123, 0xffff0000, v175
	v_pk_fma_f32 v[124:125], v[138:139], v[124:125], v[126:127]
	s_nop 0
	v_pk_fma_f32 v[122:123], v[142:143], v[122:123], v[124:125]
	s_nop 0
	v_pk_mul_f32 v[124:125], v[122:123], s[26:27] op_sel_hi:[1,0]
	v_pk_mul_f32 v[122:123], v[122:123], 0.5 op_sel_hi:[1,0]
	v_med3_f32 v124, v124, s71, v224
	v_med3_f32 v125, v125, s71, v224
	v_pk_mul_f32 v[126:127], v[124:125], v[124:125]
	s_nop 0
	v_pk_fma_f32 v[128:129], v[126:127], s[28:29], v[210:211] op_sel_hi:[1,0,0] neg_lo:[1,0,0] neg_hi:[1,0,0]
	s_nop 0
	v_pk_fma_f32 v[128:129], v[126:127], v[128:129], s[34:35] op_sel_hi:[1,1,0]
	s_nop 0
	v_pk_fma_f32 v[128:129], v[126:127], v[128:129], s[36:37] op_sel_hi:[1,1,0]
	s_nop 0
	v_pk_fma_f32 v[128:129], v[126:127], v[128:129], s[38:39] op_sel_hi:[1,1,0]
	s_nop 0
	v_pk_fma_f32 v[128:129], v[126:127], v[128:129], s[40:41] op_sel_hi:[1,1,0]
	s_nop 0
	v_pk_fma_f32 v[128:129], v[126:127], v[128:129], s[42:43] op_sel_hi:[1,1,0]
	s_nop 0
	v_pk_fma_f32 v[126:127], v[126:127], v[128:129], s[44:45] op_sel_hi:[1,1,0]
	s_nop 0
	v_pk_mul_f32 v[124:125], v[124:125], v[126:127]
	v_lshlrev_b32_e32 v126, 16, v168
	v_pk_fma_f32 v[122:123], v[122:123], v[124:125], v[122:123]
	v_and_b32_e32 v127, 0xffff0000, v168
	v_pk_mul_f32 v[118:119], v[118:119], v[122:123]
	v_cvt_pk_bf16_f32 v122, v116, v117
	v_mov_b64_e32 v[116:117], s[0:1]
	v_mad_i64_i32 v[176:177], s[0:1], v194, s67, v[116:117]
	v_cvt_pk_bf16_f32 v123, v118, v119
	v_lshl_add_u64 v[118:119], v[176:177], 0, v[180:181]
	global_store_dwordx4 v[118:119], v[120:123], off sc1
	v_mov_b32_dpp v125, v173 row_ror:2 row_mask:0xf bank_mask:0xf bound_ctrl:1
	v_mov_b32_dpp v119, v172 row_ror:1 row_mask:0xf bank_mask:0xf bound_ctrl:1
	v_mov_b32_dpp v123, v172 row_ror:2 row_mask:0xf bank_mask:0xf bound_ctrl:1
	v_mov_b32_dpp v121, v173 row_ror:1 row_mask:0xf bank_mask:0xf bound_ctrl:1
	v_mov_b32_dpp v119, v168 row_shr:1 row_mask:0xf bank_mask:0xf
	v_mov_b32_dpp v123, v168 row_shr:2 row_mask:0xf bank_mask:0xf
	v_lshlrev_b32_e32 v122, 16, v123
	v_and_b32_e32 v123, 0xffff0000, v123
	v_lshlrev_b32_e32 v118, 16, v119
	v_and_b32_e32 v119, 0xffff0000, v119
	v_pk_fma_f32 v[122:123], v[148:149], v[122:123], v[160:161]
	v_mov_b32_dpp v125, v169 row_shr:2 row_mask:0xf bank_mask:0xf
	v_pk_fma_f32 v[118:119], v[152:153], v[118:119], v[122:123]
	v_mov_b32_dpp v121, v169 row_shr:1 row_mask:0xf bank_mask:0xf
	v_pk_fma_f32 v[118:119], v[156:157], v[126:127], v[118:119]
	v_lshlrev_b32_e32 v124, 16, v125
	v_pk_mul_f32 v[122:123], v[118:119], s[26:27] op_sel_hi:[1,0]
	v_and_b32_e32 v125, 0xffff0000, v125
	v_med3_f32 v122, v122, s71, v224
	v_med3_f32 v123, v123, s71, v224
	v_pk_mul_f32 v[126:127], v[122:123], v[122:123]
	v_pk_mul_f32 v[118:119], v[118:119], 0.5 op_sel_hi:[1,0]
	v_pk_fma_f32 v[128:129], v[126:127], s[28:29], v[210:211] op_sel_hi:[1,0,0] neg_lo:[1,0,0] neg_hi:[1,0,0]
	v_lshlrev_b32_e32 v120, 16, v121
	v_pk_fma_f32 v[128:129], v[126:127], v[128:129], s[34:35] op_sel_hi:[1,1,0]
	v_and_b32_e32 v121, 0xffff0000, v121
	v_pk_fma_f32 v[128:129], v[126:127], v[128:129], s[36:37] op_sel_hi:[1,1,0]
; __device__ __forceinline__ unsigned cvt_pk_bf16(float lo, float hi) { unsigned r; asm volatile("v_cvt_pk_bf16_f32 %0, %1, %2" : "=v"(r) : "v"(lo), "v"(hi)); return r; }
;     static __device__ __forceinline__ void unpk4(const u32x2 w, float (&o)[4]) { o[0] = bf_lo(w.x); o[1] = bf_hi(w.x); o[2] = bf_lo(w.y); o[3] = bf_hi(w.y); }
;     template <int N> static __device__ __forceinline__ u32x2 dpp_prev(const u32x2 pv, const u32x2 cur) { u32x2 r; r.x = dpp_prev1<N>(pv.x, cur.x); r.y = dpp_prev1<N>(pv.y, cur.y); return r; }
;     static __device__ __forceinline__ u32x2 finish2(const float (&g0)[4], const float (&g1)[4], const float (&g2)[4], const float (&w0)[4], const float (&w1)[4], const float (&w2)[4], const float (&bb)[4],
;                                                     const f32x4 v, float rs) {
;         float h[4];
; #pragma unroll
;         for (int j = 0; j < 4; j += 2) {
;             const f32x2 gc = (f32x2){bb[j] + w0[j] * g2[j] + w1[j] * g1[j] + w2[j] * g0[j], bb[j + 1] + w0[j + 1] * g2[j + 1] + w1[j + 1] * g1[j + 1] + w2[j + 1] * g0[j + 1]};
;             const f32x2 ge = gelu_pk(gc) * ((f32x2){v[j], v[j + 1]} * rs); h[j] = ge.x; h[j + 1] = ge.y; }
;         u32x2 w; w.x = cvt_pk_bf16(h[0], h[1]); w.y = cvt_pk_bf16(h[2], h[3]); return w;
;     __device__ __forceinline__ void operator()(const f32x4 (&acc)[2][2][4][2], const Unit& u, int wr, int wc, int fr, int fq) const {
;     ...
;                 for (int m = 0; m < 4; ++m) { const u32x4 cur = gq[m]; u32x4 hw;
; #pragma unroll
;                     for (int hv = 0; hv < 2; ++hv) { const u32x2 c2 = half2(cur, hv), p2 = half2(pv, hv);
;                         const u32x2 q1 = dpp_prev<1>(p2, c2), q2 = dpp_prev<2>(p2, c2);
;                         float g0[4], g1[4], g2[4]; unpk4(c2, g0); unpk4(q1, g1); unpk4(q2, g2);
;                         const u32x2 r = finish2(g0, g1, g2, w0[hv], w1[hv], w2[hv], bb[hv], acc[ai][bj][m][hv], rs8[ai][m]);
;                         if (hv == 0) { hw.x = r.x; hw.y = r.y; } else { hw.z = r.x; hw.w = r.y; } }
;                     *(u32x4*)(H + (size_t)(R0 + fr + 16 * m) * 2816 + col8) = hw;
	v_mad_i64_i32 v[172:173], s[0:1], v192, s67, v[116:117]
	v_pk_fma_f32 v[128:129], v[126:127], v[128:129], s[38:39] op_sel_hi:[1,1,0]
	v_readlane_b32 s0, v240, 12
	v_pk_fma_f32 v[128:129], v[126:127], v[128:129], s[40:41] op_sel_hi:[1,1,0]
	v_readlane_b32 s1, v240, 13
	v_pk_fma_f32 v[128:129], v[126:127], v[128:129], s[42:43] op_sel_hi:[1,1,0]
	s_nop 0
	v_pk_fma_f32 v[126:127], v[126:127], v[128:129], s[44:45] op_sel_hi:[1,1,0]
	s_nop 0
	v_pk_mul_f32 v[122:123], v[122:123], v[126:127]
	s_nop 0
	v_pk_fma_f32 v[118:119], v[118:119], v[122:123], v[118:119]
	v_pk_fma_f32 v[122:123], v[150:151], v[124:125], v[162:163]
	v_pk_mul_f32 v[112:113], v[112:113], v[118:119]
	v_lshlrev_b32_e32 v118, 16, v169
	v_and_b32_e32 v119, 0xffff0000, v169
	v_pk_fma_f32 v[120:121], v[154:155], v[120:121], v[122:123]
	v_cvt_pk_bf16_f32 v112, v112, v113
	s_nop 0
	v_pk_fma_f32 v[118:119], v[158:159], v[118:119], v[120:121]
	s_nop 0
	v_pk_mul_f32 v[120:121], v[118:119], s[26:27] op_sel_hi:[1,0]
	v_pk_mul_f32 v[118:119], v[118:119], 0.5 op_sel_hi:[1,0]
	v_med3_f32 v120, v120, s71, v224
	v_med3_f32 v121, v121, s71, v224
	v_pk_mul_f32 v[122:123], v[120:121], v[120:121]
	s_nop 0
	v_pk_fma_f32 v[124:125], v[122:123], s[28:29], v[210:211] op_sel_hi:[1,0,0] neg_lo:[1,0,0] neg_hi:[1,0,0]
	s_nop 0
	v_pk_fma_f32 v[124:125], v[122:123], v[124:125], s[34:35] op_sel_hi:[1,1,0]
	s_nop 0
	v_pk_fma_f32 v[124:125], v[122:123], v[124:125], s[36:37] op_sel_hi:[1,1,0]
	s_nop 0
	v_pk_fma_f32 v[124:125], v[122:123], v[124:125], s[38:39] op_sel_hi:[1,1,0]
	s_nop 0
	v_pk_fma_f32 v[124:125], v[122:123], v[124:125], s[40:41] op_sel_hi:[1,1,0]
	s_nop 0
	v_pk_fma_f32 v[124:125], v[122:123], v[124:125], s[42:43] op_sel_hi:[1,1,0]
	s_nop 0
	v_pk_fma_f32 v[122:123], v[122:123], v[124:125], s[44:45] op_sel_hi:[1,1,0]
	v_lshlrev_b32_e32 v124, 16, v170
	v_pk_mul_f32 v[120:121], v[120:121], v[122:123]
	v_and_b32_e32 v125, 0xffff0000, v170
	v_pk_fma_f32 v[118:119], v[118:119], v[120:121], v[118:119]
	v_mov_b32_dpp v121, v174 row_ror:2 row_mask:0xf bank_mask:0xf bound_ctrl:1
	v_pk_mul_f32 v[114:115], v[114:115], v[118:119]
	v_mov_b32_dpp v123, v175 row_ror:2 row_mask:0xf bank_mask:0xf bound_ctrl:1
	v_cvt_pk_bf16_f32 v113, v114, v115
	v_mov_b32_dpp v121, v170 row_shr:2 row_mask:0xf bank_mask:0xf
	v_mov_b32_dpp v115, v174 row_ror:1 row_mask:0xf bank_mask:0xf bound_ctrl:1
	v_lshlrev_b32_e32 v120, 16, v121
	v_and_b32_e32 v121, 0xffff0000, v121
	v_mov_b32_dpp v115, v170 row_shr:1 row_mask:0xf bank_mask:0xf
	v_lshlrev_b32_e32 v114, 16, v115
	v_and_b32_e32 v115, 0xffff0000, v115
	v_pk_fma_f32 v[120:121], v[132:133], v[120:121], v[144:145]
	v_mov_b32_dpp v119, v175 row_ror:1 row_mask:0xf bank_mask:0xf bound_ctrl:1
	v_pk_fma_f32 v[114:115], v[136:137], v[114:115], v[120:121]
	v_mov_b32_dpp v123, v171 row_shr:2 row_mask:0xf bank_mask:0xf
	v_pk_fma_f32 v[114:115], v[140:141], v[124:125], v[114:115]
	v_mov_b32_dpp v119, v171 row_shr:1 row_mask:0xf bank_mask:0xf
	v_pk_mul_f32 v[120:121], v[114:115], s[26:27] op_sel_hi:[1,0]
	v_lshlrev_b32_e32 v122, 16, v123
	v_med3_f32 v120, v120, s71, v224
	v_med3_f32 v121, v121, s71, v224
	v_pk_mul_f32 v[124:125], v[120:121], v[120:121]
	v_and_b32_e32 v123, 0xffff0000, v123
	v_pk_fma_f32 v[126:127], v[124:125], s[28:29], v[210:211] op_sel_hi:[1,0,0] neg_lo:[1,0,0] neg_hi:[1,0,0]
	v_pk_mul_f32 v[114:115], v[114:115], 0.5 op_sel_hi:[1,0]
	v_pk_fma_f32 v[126:127], v[124:125], v[126:127], s[34:35] op_sel_hi:[1,1,0]
	v_lshlrev_b32_e32 v118, 16, v119
	v_pk_fma_f32 v[126:127], v[124:125], v[126:127], s[36:37] op_sel_hi:[1,1,0]
	v_and_b32_e32 v119, 0xffff0000, v119
	v_pk_fma_f32 v[126:127], v[124:125], v[126:127], s[38:39] op_sel_hi:[1,1,0]
	s_nop 0
	v_pk_fma_f32 v[126:127], v[124:125], v[126:127], s[40:41] op_sel_hi:[1,1,0]
	s_nop 0
	v_pk_fma_f32 v[126:127], v[124:125], v[126:127], s[42:43] op_sel_hi:[1,1,0]
	s_nop 0
	v_pk_fma_f32 v[124:125], v[124:125], v[126:127], s[44:45] op_sel_hi:[1,1,0]
	s_nop 0
	v_pk_mul_f32 v[120:121], v[120:121], v[124:125]
	s_nop 0
	v_pk_fma_f32 v[114:115], v[114:115], v[120:121], v[114:115]
	v_pk_fma_f32 v[120:121], v[134:135], v[122:123], v[146:147]
	v_pk_mul_f32 v[108:109], v[108:109], v[114:115]
	v_lshlrev_b32_e32 v114, 16, v171
	v_and_b32_e32 v115, 0xffff0000, v171
	v_pk_fma_f32 v[118:119], v[138:139], v[118:119], v[120:121]
	s_nop 0
	v_pk_fma_f32 v[114:115], v[142:143], v[114:115], v[118:119]
	s_nop 0
	v_pk_mul_f32 v[118:119], v[114:115], s[26:27] op_sel_hi:[1,0]
	v_pk_mul_f32 v[114:115], v[114:115], 0.5 op_sel_hi:[1,0]
	v_med3_f32 v118, v118, s71, v224
	v_med3_f32 v119, v119, s71, v224
	v_pk_mul_f32 v[120:121], v[118:119], v[118:119]
	s_nop 0
	v_pk_fma_f32 v[122:123], v[120:121], s[28:29], v[210:211] op_sel_hi:[1,0,0] neg_lo:[1,0,0] neg_hi:[1,0,0]
	s_nop 0
	v_pk_fma_f32 v[122:123], v[120:121], v[122:123], s[34:35] op_sel_hi:[1,1,0]
	s_nop 0
	v_pk_fma_f32 v[122:123], v[120:121], v[122:123], s[36:37] op_sel_hi:[1,1,0]
	s_nop 0
	v_pk_fma_f32 v[122:123], v[120:121], v[122:123], s[38:39] op_sel_hi:[1,1,0]
	s_nop 0
	v_pk_fma_f32 v[122:123], v[120:121], v[122:123], s[40:41] op_sel_hi:[1,1,0]
	s_nop 0
	v_pk_fma_f32 v[122:123], v[120:121], v[122:123], s[42:43] op_sel_hi:[1,1,0]
	s_nop 0
	v_pk_fma_f32 v[120:121], v[120:121], v[122:123], s[44:45] op_sel_hi:[1,1,0]
	s_nop 0
	v_pk_mul_f32 v[118:119], v[118:119], v[120:121]
	s_nop 0
	v_pk_fma_f32 v[114:115], v[114:115], v[118:119], v[114:115]
	v_lshlrev_b32_e32 v118, 16, v164
	v_pk_mul_f32 v[110:111], v[110:111], v[114:115]
	v_cvt_pk_bf16_f32 v114, v108, v109
	v_lshl_add_u64 v[108:109], v[172:173], 0, v[180:181]
	v_cvt_pk_bf16_f32 v115, v110, v111
	global_store_dwordx4 v[108:109], v[112:115], off sc1
; __device__ __forceinline__ unsigned cvt_pk_bf16(float lo, float hi) { unsigned r; asm volatile("v_cvt_pk_bf16_f32 %0, %1, %2" : "=v"(r) : "v"(lo), "v"(hi)); return r; }
;     static __device__ __forceinline__ void unpk4(const u32x2 w, float (&o)[4]) { o[0] = bf_lo(w.x); o[1] = bf_hi(w.x); o[2] = bf_lo(w.y); o[3] = bf_hi(w.y); }
;     template <int N> static __device__ __forceinline__ u32x2 dpp_prev(const u32x2 pv, const u32x2 cur) { u32x2 r; r.x = dpp_prev1<N>(pv.x, cur.x); r.y = dpp_prev1<N>(pv.y, cur.y); return r; }
;     static __device__ __forceinline__ u32x2 finish2(const float (&g0)[4], const float (&g1)[4], const float (&g2)[4], const float (&w0)[4], const float (&w1)[4], const float (&w2)[4], const float (&bb)[4],
;                                                     const f32x4 v, float rs) {
;         float h[4];
; #pragma unroll
;         for (int j = 0; j < 4; j += 2) {
;             const f32x2 gc = (f32x2){bb[j] + w0[j] * g2[j] + w1[j] * g1[j] + w2[j] * g0[j], bb[j + 1] + w0[j + 1] * g2[j + 1] + w1[j + 1] * g1[j + 1] + w2[j + 1] * g0[j + 1]};
;             const f32x2 ge = gelu_pk(gc) * ((f32x2){v[j], v[j + 1]} * rs); h[j] = ge.x; h[j + 1] = ge.y; }
;         u32x2 w; w.x = cvt_pk_bf16(h[0], h[1]); w.y = cvt_pk_bf16(h[2], h[3]); return w;
;     __device__ __forceinline__ void operator()(const f32x4 (&acc)[2][2][4][2], const Unit& u, int wr, int wc, int fr, int fq) const {
;     ...
;                 for (int m = 0; m < 4; ++m) { const u32x4 cur = gq[m]; u32x4 hw;
; #pragma unroll
;                     for (int hv = 0; hv < 2; ++hv) { const u32x2 c2 = half2(cur, hv), p2 = half2(pv, hv);
;                         const u32x2 q1 = dpp_prev<1>(p2, c2), q2 = dpp_prev<2>(p2, c2);
;                         float g0[4], g1[4], g2[4]; unpk4(c2, g0); unpk4(q1, g1); unpk4(q2, g2);
;                         const u32x2 r = finish2(g0, g1, g2, w0[hv], w1[hv], w2[hv], bb[hv], acc[ai][bj][m][hv], rs8[ai][m]);
;                         if (hv == 0) { hw.x = r.x; hw.y = r.y; } else { hw.z = r.x; hw.w = r.y; } }
;                     *(u32x4*)(H + (size_t)(R0 + fr + 16 * m) * 2816 + col8) = hw;
	v_and_b32_e32 v119, 0xffff0000, v164
	v_mov_b32_dpp v109, v168 row_ror:1 row_mask:0xf bank_mask:0xf bound_ctrl:1
	v_mov_b32_dpp v113, v168 row_ror:2 row_mask:0xf bank_mask:0xf bound_ctrl:1
	v_mov_b32_dpp v115, v169 row_ror:2 row_mask:0xf bank_mask:0xf bound_ctrl:1
	v_mov_b32_dpp v109, v164 row_shr:1 row_mask:0xf bank_mask:0xf
	v_mov_b32_dpp v113, v164 row_shr:2 row_mask:0xf bank_mask:0xf
	v_lshlrev_b32_e32 v112, 16, v113
	v_and_b32_e32 v113, 0xffff0000, v113
	v_lshlrev_b32_e32 v108, 16, v109
	v_and_b32_e32 v109, 0xffff0000, v109
	v_pk_fma_f32 v[112:113], v[148:149], v[112:113], v[160:161]
	v_mov_b32_dpp v111, v169 row_ror:1 row_mask:0xf bank_mask:0xf bound_ctrl:1
	v_pk_fma_f32 v[108:109], v[152:153], v[108:109], v[112:113]
	v_mov_b32_dpp v115, v165 row_shr:2 row_mask:0xf bank_mask:0xf
	v_pk_fma_f32 v[108:109], v[156:157], v[118:119], v[108:109]
	v_mov_b32_dpp v111, v165 row_shr:1 row_mask:0xf bank_mask:0xf
	v_pk_mul_f32 v[112:113], v[108:109], s[26:27] op_sel_hi:[1,0]
	v_lshlrev_b32_e32 v114, 16, v115
	v_med3_f32 v112, v112, s71, v224
	v_med3_f32 v113, v113, s71, v224
	v_pk_mul_f32 v[118:119], v[112:113], v[112:113]
	v_and_b32_e32 v115, 0xffff0000, v115
	v_pk_fma_f32 v[120:121], v[118:119], s[28:29], v[210:211] op_sel_hi:[1,0,0] neg_lo:[1,0,0] neg_hi:[1,0,0]
	v_pk_mul_f32 v[108:109], v[108:109], 0.5 op_sel_hi:[1,0]
	v_pk_fma_f32 v[120:121], v[118:119], v[120:121], s[34:35] op_sel_hi:[1,1,0]
	v_lshlrev_b32_e32 v110, 16, v111
	v_pk_fma_f32 v[120:121], v[118:119], v[120:121], s[36:37] op_sel_hi:[1,1,0]
	v_and_b32_e32 v111, 0xffff0000, v111
	v_pk_fma_f32 v[120:121], v[118:119], v[120:121], s[38:39] op_sel_hi:[1,1,0]
	s_nop 0
	v_pk_fma_f32 v[120:121], v[118:119], v[120:121], s[40:41] op_sel_hi:[1,1,0]
	s_nop 0
	v_pk_fma_f32 v[120:121], v[118:119], v[120:121], s[42:43] op_sel_hi:[1,1,0]
	s_nop 0
	v_pk_fma_f32 v[118:119], v[118:119], v[120:121], s[44:45] op_sel_hi:[1,1,0]
	s_nop 0
	v_pk_mul_f32 v[112:113], v[112:113], v[118:119]
	s_nop 0
	v_pk_fma_f32 v[108:109], v[108:109], v[112:113], v[108:109]
	v_pk_fma_f32 v[112:113], v[150:151], v[114:115], v[162:163]
	v_pk_mul_f32 v[104:105], v[104:105], v[108:109]
	v_lshlrev_b32_e32 v108, 16, v165
	v_and_b32_e32 v109, 0xffff0000, v165
	v_pk_fma_f32 v[110:111], v[154:155], v[110:111], v[112:113]
	v_cvt_pk_bf16_f32 v120, v104, v105
	v_mov_b32_dpp v105, v170 row_ror:1 row_mask:0xf bank_mask:0xf bound_ctrl:1
	v_pk_fma_f32 v[108:109], v[158:159], v[108:109], v[110:111]
	s_nop 0
	v_pk_mul_f32 v[110:111], v[108:109], s[26:27] op_sel_hi:[1,0]
	v_pk_mul_f32 v[108:109], v[108:109], 0.5 op_sel_hi:[1,0]
	v_med3_f32 v110, v110, s71, v224
	v_med3_f32 v111, v111, s71, v224
	v_pk_mul_f32 v[112:113], v[110:111], v[110:111]
	v_mov_b32_dpp v105, v166 row_shr:1 row_mask:0xf bank_mask:0xf
	v_pk_fma_f32 v[114:115], v[112:113], s[28:29], v[210:211] op_sel_hi:[1,0,0] neg_lo:[1,0,0] neg_hi:[1,0,0]
	v_lshlrev_b32_e32 v104, 16, v105
	v_pk_fma_f32 v[114:115], v[112:113], v[114:115], s[34:35] op_sel_hi:[1,1,0]
	v_and_b32_e32 v105, 0xffff0000, v105
	v_pk_fma_f32 v[114:115], v[112:113], v[114:115], s[36:37] op_sel_hi:[1,1,0]
	s_nop 0
	v_pk_fma_f32 v[114:115], v[112:113], v[114:115], s[38:39] op_sel_hi:[1,1,0]
	s_nop 0
	v_pk_fma_f32 v[114:115], v[112:113], v[114:115], s[40:41] op_sel_hi:[1,1,0]
	s_nop 0
	v_pk_fma_f32 v[114:115], v[112:113], v[114:115], s[42:43] op_sel_hi:[1,1,0]
	s_nop 0
	v_pk_fma_f32 v[112:113], v[112:113], v[114:115], s[44:45] op_sel_hi:[1,1,0]
	s_nop 0
	v_pk_mul_f32 v[110:111], v[110:111], v[112:113]
	v_lshlrev_b32_e32 v112, 16, v166
	v_pk_fma_f32 v[108:109], v[108:109], v[110:111], v[108:109]
	v_and_b32_e32 v113, 0xffff0000, v166
	v_pk_mul_f32 v[106:107], v[106:107], v[108:109]
	v_mov_b32_dpp v109, v170 row_ror:2 row_mask:0xf bank_mask:0xf bound_ctrl:1
	v_mov_b32_dpp v111, v171 row_ror:2 row_mask:0xf bank_mask:0xf bound_ctrl:1
	v_cvt_pk_bf16_f32 v121, v106, v107
	v_mov_b32_dpp v107, v171 row_ror:1 row_mask:0xf bank_mask:0xf bound_ctrl:1
	v_mov_b32_dpp v109, v166 row_shr:2 row_mask:0xf bank_mask:0xf
;     static __device__ __forceinline__ void unpk4(const u32x2 w, float (&o)[4]) { o[0] = bf_lo(w.x); o[1] = bf_hi(w.x); o[2] = bf_lo(w.y); o[3] = bf_hi(w.y); }
;     template <int N> static __device__ __forceinline__ u32x2 dpp_prev(const u32x2 pv, const u32x2 cur) { u32x2 r; r.x = dpp_prev1<N>(pv.x, cur.x); r.y = dpp_prev1<N>(pv.y, cur.y); return r; }
;     __device__ __forceinline__ void operator()(const f32x4 (&acc)[2][2][4][2], const Unit& u, int wr, int wc, int fr, int fq) const {
;     ...
;             for (int ai = 0; ai < 2; ++ai) { const int R0 = u.rb + ai * HALF + wr * 64; const bf16_t* gp = G + (size_t)(R0 + fr) * 2816 + col8;
;                 u32x4 gq[4], prv = (u32x4){0u, 0u, 0u, 0u};
; #pragma unroll
;                 for (int m = 0; m < 4; ++m) gq[m] = *(const u32x4*)(gp + (size_t)m * 16 * 2816);
;                 if ((R0 & 8191) != 0) prv = *(const u32x4*)(gp - (size_t)16 * 2816);
;                 u32x4 pv = prv;
; #pragma unroll
;                 for (int m = 0; m < 4; ++m) { const u32x4 cur = gq[m]; u32x4 hw;
; #pragma unroll
;                     for (int hv = 0; hv < 2; ++hv) { const u32x2 c2 = half2(cur, hv), p2 = half2(pv, hv);
;                         const u32x2 q1 = dpp_prev<1>(p2, c2), q2 = dpp_prev<2>(p2, c2);
;                         float g0[4], g1[4], g2[4]; unpk4(c2, g0); unpk4(q1, g1); unpk4(q2, g2);
;                         const u32x2 r = finish2(g0, g1, g2, w0[hv], w1[hv], w2[hv], bb[hv], acc[ai][bj][m][hv], rs8[ai][m]);
;                         if (hv == 0) { hw.x = r.x; hw.y = r.y; } else { hw.z = r.x; hw.w = r.y; } }
;                     *(u32x4*)(H + (size_t)(R0 + fr + 16 * m) * 2816 + col8) = hw;
	v_lshlrev_b32_e32 v108, 16, v109
	v_and_b32_e32 v109, 0xffff0000, v109
	v_pk_fma_f32 v[108:109], v[132:133], v[108:109], v[144:145]
	v_mov_b32_dpp v111, v167 row_shr:2 row_mask:0xf bank_mask:0xf
	v_pk_fma_f32 v[104:105], v[136:137], v[104:105], v[108:109]
	v_mov_b32_dpp v107, v167 row_shr:1 row_mask:0xf bank_mask:0xf
	v_pk_fma_f32 v[104:105], v[140:141], v[112:113], v[104:105]
	v_lshlrev_b32_e32 v110, 16, v111
	v_pk_mul_f32 v[108:109], v[104:105], s[26:27] op_sel_hi:[1,0]
	v_and_b32_e32 v111, 0xffff0000, v111
	v_med3_f32 v108, v108, s71, v224
	v_med3_f32 v109, v109, s71, v224
	v_pk_mul_f32 v[112:113], v[108:109], v[108:109]
	v_pk_mul_f32 v[104:105], v[104:105], 0.5 op_sel_hi:[1,0]
	v_pk_fma_f32 v[114:115], v[112:113], s[28:29], v[210:211] op_sel_hi:[1,0,0] neg_lo:[1,0,0] neg_hi:[1,0,0]
	v_lshlrev_b32_e32 v106, 16, v107
	v_pk_fma_f32 v[114:115], v[112:113], v[114:115], s[34:35] op_sel_hi:[1,1,0]
	v_and_b32_e32 v107, 0xffff0000, v107
	v_pk_fma_f32 v[114:115], v[112:113], v[114:115], s[36:37] op_sel_hi:[1,1,0]
	s_nop 0
	v_pk_fma_f32 v[114:115], v[112:113], v[114:115], s[38:39] op_sel_hi:[1,1,0]
	s_nop 0
	v_pk_fma_f32 v[114:115], v[112:113], v[114:115], s[40:41] op_sel_hi:[1,1,0]
	s_nop 0
	v_pk_fma_f32 v[114:115], v[112:113], v[114:115], s[42:43] op_sel_hi:[1,1,0]
	s_nop 0
	v_pk_fma_f32 v[112:113], v[112:113], v[114:115], s[44:45] op_sel_hi:[1,1,0]
	s_nop 0
	v_pk_mul_f32 v[108:109], v[108:109], v[112:113]
	s_nop 0
	v_pk_fma_f32 v[104:105], v[104:105], v[108:109], v[104:105]
	v_pk_fma_f32 v[108:109], v[134:135], v[110:111], v[146:147]
	v_pk_mul_f32 v[100:101], v[100:101], v[104:105]
	v_lshlrev_b32_e32 v104, 16, v167
	v_and_b32_e32 v105, 0xffff0000, v167
	v_pk_fma_f32 v[106:107], v[138:139], v[106:107], v[108:109]
	v_cvt_pk_bf16_f32 v122, v100, v101
	v_mov_b64_e32 v[100:101], s[0:1]
	v_pk_fma_f32 v[104:105], v[142:143], v[104:105], v[106:107]
	v_mad_i64_i32 v[164:165], s[0:1], v1, s67, v[100:101]
	v_pk_mul_f32 v[106:107], v[104:105], s[26:27] op_sel_hi:[1,0]
	v_lshl_add_u64 v[118:119], v[164:165], 0, v[180:181]
	v_med3_f32 v106, v106, s71, v224
	v_med3_f32 v107, v107, s71, v224
	v_pk_mul_f32 v[108:109], v[106:107], v[106:107]
	v_pk_mul_f32 v[104:105], v[104:105], 0.5 op_sel_hi:[1,0]
	v_pk_fma_f32 v[110:111], v[108:109], s[28:29], v[210:211] op_sel_hi:[1,0,0] neg_lo:[1,0,0] neg_hi:[1,0,0]
	v_add_co_u32_e32 v100, vcc, s45, v118
	v_pk_fma_f32 v[110:111], v[108:109], v[110:111], s[34:35] op_sel_hi:[1,1,0]
	s_nop 0
	v_addc_co_u32_e32 v101, vcc, 0, v119, vcc
	v_pk_fma_f32 v[110:111], v[108:109], v[110:111], s[36:37] op_sel_hi:[1,1,0]
	v_mad_i64_i32 v[166:167], s[0:1], v190, s67, v[116:117]
	v_pk_fma_f32 v[110:111], v[108:109], v[110:111], s[38:39] op_sel_hi:[1,1,0]
	s_and_b32 s0, s47, 0x1fff
	v_pk_fma_f32 v[110:111], v[108:109], v[110:111], s[40:41] op_sel_hi:[1,1,0]
	s_cmp_lg_u32 s0, 0
	v_pk_fma_f32 v[110:111], v[108:109], v[110:111], s[42:43] op_sel_hi:[1,1,0]
	v_lshl_add_u64 v[116:117], v[166:167], 0, v[180:181]
	v_pk_fma_f32 v[108:109], v[108:109], v[110:111], s[44:45] op_sel_hi:[1,1,0]
	s_cselect_b64 s[8:9], -1, 0
	v_pk_mul_f32 v[106:107], v[106:107], v[108:109]
	s_cmp_eq_u32 s0, 0
	v_pk_fma_f32 v[104:105], v[104:105], v[106:107], v[104:105]
	s_nop 0
	v_pk_mul_f32 v[102:103], v[102:103], v[104:105]
	s_nop 0
	v_cvt_pk_bf16_f32 v123, v102, v103
	global_load_dwordx4 v[112:115], v[118:119], off
	global_load_dwordx4 v[108:111], v[100:101], off
	v_add_co_u32_e32 v100, vcc, 0x2c000, v118
	s_nop 1
	v_addc_co_u32_e32 v101, vcc, 0, v119, vcc
	v_add_co_u32_e32 v102, vcc, 0x42000, v118
	s_nop 1
	v_addc_co_u32_e32 v103, vcc, 0, v119, vcc
	global_load_dwordx4 v[104:107], v[100:101], off
	s_nop 0
	global_load_dwordx4 v[100:103], v[102:103], off
	s_nop 0
	global_store_dwordx4 v[116:117], v[120:123], off sc1
	s_cbranch_scc1 .LBB0_3147
	v_add_co_u32_e32 v116, vcc, 0xfffea000, v118
	s_nop 1
	v_addc_co_u32_e32 v117, vcc, -1, v119, vcc
	global_load_dwordx4 v[116:119], v[116:117], off
	s_branch .LBB0_3148

;     static __device__ __forceinline__ void unpk4(const u32x2 w, float (&o)[4]) { o[0] = bf_lo(w.x); o[1] = bf_hi(w.x); o[2] = bf_lo(w.y); o[3] = bf_hi(w.y); }
;     template <int N> static __device__ __forceinline__ u32x2 dpp_prev(const u32x2 pv, const u32x2 cur) { u32x2 r; r.x = dpp_prev1<N>(pv.x, cur.x); r.y = dpp_prev1<N>(pv.y, cur.y); return r; }
;     __device__ __forceinline__ void operator()(const f32x4 (&acc)[2][2][4][2], const Unit& u, int wr, int wc, int fr, int fq) const {
;     ...
;         for (int ai = 0; ai < 2; ++ai)
; #pragma unroll
;             for (int m = 0; m < 4; ++m) rs8[ai][m] = rsqrtf(SS[u.rb + (u.half ? 0 : ai * HALF) + wr * 64 + fr + 16 * m] * (1.f / 1024.f) + 1e-6f);
;     ...
;                 for (int m = 0; m < 4; ++m) { const u32x4 cur = gq[m]; u32x4 hw;
; #pragma unroll
;                     for (int hv = 0; hv < 2; ++hv) { const u32x2 c2 = half2(cur, hv), p2 = half2(pv, hv);
;                         const u32x2 q1 = dpp_prev<1>(p2, c2), q2 = dpp_prev<2>(p2, c2);
;                         float g0[4], g1[4], g2[4]; unpk4(c2, g0); unpk4(q1, g1); unpk4(q2, g2);
;                         const u32x2 r = finish2(g0, g1, g2, w0[hv], w1[hv], w2[hv], bb[hv], acc[ai][bj][m][hv], rs8[ai][m]);
;                         if (hv == 0) { hw.x = r.x; hw.y = r.y; } else { hw.z = r.x; hw.w = r.y; } }
;                     *(u32x4*)(H + (size_t)(R0 + fr + 16 * m) * 2816 + col8) = hw;
.LBB0_3148:
	v_fmamk_f32 v120, v189, 0x3a800000, v223
	v_mul_f32_e32 v121, 0x4b800000, v120
	v_cmp_gt_f32_e32 vcc, s66, v120
	v_fmamk_f32 v3, v3, 0x3a800000, v223
	s_waitcnt vmcnt(0)
	v_mov_b32_dpp v127, v117 row_ror:2 row_mask:0xf bank_mask:0xf bound_ctrl:1
	v_cndmask_b32_e32 v120, v120, v121, vcc
	v_rsq_f32_e32 v122, v120
	v_fmamk_f32 v120, v187, 0x3a800000, v223
	v_mul_f32_e32 v121, 0x4b800000, v120
	v_cmp_gt_f32_e64 s[0:1], s66, v120
	v_mul_f32_e32 v124, 0x45800000, v122
	v_cndmask_b32_e32 v128, v122, v124, vcc
	v_cndmask_b32_e64 v120, v120, v121, s[0:1]
	v_mul_f32_e32 v124, 0x4b800000, v3
	v_cmp_gt_f32_e32 vcc, s66, v3
	v_rsq_f32_e32 v123, v120
	v_mad_i64_i32 v[120:121], s[6:7], v1, s67, 0
	v_cndmask_b32_e32 v3, v3, v124, vcc
	v_fmamk_f32 v124, v185, 0x3a800000, v223
	v_mul_f32_e32 v125, 0x4b800000, v124
	v_cmp_gt_f32_e64 s[6:7], s66, v124
	v_rsq_f32_e32 v3, v3
	v_mul_f32_e32 v122, 0x45800000, v123
	v_cndmask_b32_e64 v124, v124, v125, s[6:7]
	v_rsq_f32_e32 v125, v124
	v_cndmask_b32_e64 v126, v123, v122, s[0:1]
	v_mul_f32_e32 v122, 0x45800000, v3
	v_cndmask_b32_e32 v124, v3, v122, vcc
	v_mul_f32_e32 v3, 0x45800000, v125
	v_cndmask_b32_e64 v122, v125, v3, s[6:7]
	v_mov_b32_dpp v125, v116 row_ror:2 row_mask:0xf bank_mask:0xf bound_ctrl:1
	v_mov_b32_dpp v3, v116 row_ror:1 row_mask:0xf bank_mask:0xf bound_ctrl:1
	v_mov_b32_dpp v123, v117 row_ror:1 row_mask:0xf bank_mask:0xf bound_ctrl:1
	v_mov_b32_dpp v125, v112 row_shr:2 row_mask:0xf bank_mask:0xf
	v_mov_b32_dpp v3, v112 row_shr:1 row_mask:0xf bank_mask:0xf
	v_lshlrev_b32_e32 v170, 16, v125
	v_and_b32_e32 v171, 0xffff0000, v125
	v_lshlrev_b32_e32 v116, 16, v3
	v_and_b32_e32 v117, 0xffff0000, v3
	v_pk_fma_f32 v[170:171], v[148:149], v[170:171], v[160:161]
	v_lshlrev_b32_e32 v178, 16, v112
	v_and_b32_e32 v179, 0xffff0000, v112
	v_pk_fma_f32 v[116:117], v[152:153], v[116:117], v[170:171]
	v_mov_b32_dpp v127, v113 row_shr:2 row_mask:0xf bank_mask:0xf
	v_pk_fma_f32 v[170:171], v[156:157], v[178:179], v[116:117]
	v_mov_b32_dpp v123, v113 row_shr:1 row_mask:0xf bank_mask:0xf
	v_pk_mul_f32 v[116:117], v[170:171], s[26:27] op_sel_hi:[1,0]
	v_lshlrev_b32_e32 v174, 16, v127
	v_med3_f32 v178, v116, s71, v224
	v_med3_f32 v179, v117, s71, v224
	v_pk_mul_f32 v[182:183], v[178:179], v[178:179]
	v_mov_b64_e32 v[116:117], s[30:31]
	v_pk_fma_f32 v[190:191], v[182:183], s[28:29], v[116:117] op_sel_hi:[1,0,0] neg_lo:[1,0,0] neg_hi:[1,0,0]
	v_and_b32_e32 v175, 0xffff0000, v127
	v_pk_fma_f32 v[190:191], v[182:183], v[190:191], s[34:35] op_sel_hi:[1,1,0]
	v_pk_mul_f32 v[170:171], v[170:171], 0.5 op_sel_hi:[1,0]
	v_pk_fma_f32 v[190:191], v[182:183], v[190:191], s[36:37] op_sel_hi:[1,1,0]
	v_lshlrev_b32_e32 v168, 16, v123
	v_pk_fma_f32 v[190:191], v[182:183], v[190:191], s[38:39] op_sel_hi:[1,1,0]
	v_and_b32_e32 v169, 0xffff0000, v123
	v_pk_fma_f32 v[190:191], v[182:183], v[190:191], s[40:41] op_sel_hi:[1,1,0]
	v_pk_mul_f32 v[96:97], v[96:97], v[128:129] op_sel_hi:[1,0]
	v_pk_fma_f32 v[190:191], v[182:183], v[190:191], s[42:43] op_sel_hi:[1,1,0]
	v_pk_fma_f32 v[174:175], v[150:151], v[174:175], v[162:163]
	v_pk_fma_f32 v[182:183], v[182:183], v[190:191], s[44:45] op_sel_hi:[1,1,0]
	v_pk_fma_f32 v[168:169], v[154:155], v[168:169], v[174:175]
	v_pk_mul_f32 v[178:179], v[178:179], v[182:183]
	v_mov_b32_dpp v125, v118 row_ror:2 row_mask:0xf bank_mask:0xf bound_ctrl:1
	v_pk_fma_f32 v[170:171], v[170:171], v[178:179], v[170:171]
	v_pk_mul_f32 v[98:99], v[98:99], v[128:129] op_sel_hi:[1,0]
	v_pk_mul_f32 v[96:97], v[96:97], v[170:171]
	v_lshlrev_b32_e32 v170, 16, v113
	v_and_b32_e32 v171, 0xffff0000, v113
	v_pk_fma_f32 v[168:169], v[158:159], v[170:171], v[168:169]
	v_mov_b32_dpp v3, v118 row_ror:1 row_mask:0xf bank_mask:0xf bound_ctrl:1
	v_pk_mul_f32 v[170:171], v[168:169], s[26:27] op_sel_hi:[1,0]
	v_pk_mul_f32 v[168:169], v[168:169], 0.5 op_sel_hi:[1,0]
	v_med3_f32 v170, v170, s71, v224
	v_med3_f32 v171, v171, s71, v224
	v_pk_mul_f32 v[174:175], v[170:171], v[170:171]
	v_mov_b32_dpp v125, v114 row_shr:2 row_mask:0xf bank_mask:0xf
	v_pk_fma_f32 v[178:179], v[174:175], s[28:29], v[116:117] op_sel_hi:[1,0,0] neg_lo:[1,0,0] neg_hi:[1,0,0]
	v_mov_b32_dpp v3, v114 row_shr:1 row_mask:0xf bank_mask:0xf
	v_pk_fma_f32 v[178:179], v[174:175], v[178:179], s[34:35] op_sel_hi:[1,1,0]
	v_cvt_pk_bf16_f32 v96, v96, v97
	v_mov_b32_dpp v127, v119 row_ror:2 row_mask:0xf bank_mask:0xf bound_ctrl:1
	v_pk_fma_f32 v[178:179], v[174:175], v[178:179], s[36:37] op_sel_hi:[1,1,0]
	v_mov_b32_dpp v123, v119 row_ror:1 row_mask:0xf bank_mask:0xf bound_ctrl:1
	v_pk_fma_f32 v[178:179], v[174:175], v[178:179], s[38:39] op_sel_hi:[1,1,0]
	v_mov_b32_dpp v127, v115 row_shr:2 row_mask:0xf bank_mask:0xf
	v_pk_fma_f32 v[178:179], v[174:175], v[178:179], s[40:41] op_sel_hi:[1,1,0]
	v_mov_b32_dpp v123, v115 row_shr:1 row_mask:0xf bank_mask:0xf
	v_pk_fma_f32 v[178:179], v[174:175], v[178:179], s[42:43] op_sel_hi:[1,1,0]
	v_lshlrev_b32_e32 v118, 16, v123
	v_pk_fma_f32 v[174:175], v[174:175], v[178:179], s[44:45] op_sel_hi:[1,1,0]
	v_and_b32_e32 v119, 0xffff0000, v123
	v_pk_mul_f32 v[170:171], v[170:171], v[174:175]
	v_lshlrev_b32_e32 v174, 16, v114
	v_pk_fma_f32 v[168:169], v[168:169], v[170:171], v[168:169]
	v_and_b32_e32 v175, 0xffff0000, v114
	v_pk_mul_f32 v[98:99], v[98:99], v[168:169]
	v_lshlrev_b32_e32 v168, 16, v125
	v_and_b32_e32 v169, 0xffff0000, v125
	v_cvt_pk_bf16_f32 v97, v98, v99
	v_lshlrev_b32_e32 v98, 16, v3
	v_and_b32_e32 v99, 0xffff0000, v3
	v_pk_fma_f32 v[168:169], v[132:133], v[168:169], v[144:145]
	v_lshlrev_b32_e32 v170, 16, v127
	v_pk_fma_f32 v[98:99], v[136:137], v[98:99], v[168:169]
	v_and_b32_e32 v171, 0xffff0000, v127
; __device__ __forceinline__ unsigned cvt_pk_bf16(float lo, float hi) { unsigned r; asm volatile("v_cvt_pk_bf16_f32 %0, %1, %2" : "=v"(r) : "v"(lo), "v"(hi)); return r; }
;     static __device__ __forceinline__ void unpk4(const u32x2 w, float (&o)[4]) { o[0] = bf_lo(w.x); o[1] = bf_hi(w.x); o[2] = bf_lo(w.y); o[3] = bf_hi(w.y); }
;     template <int N> static __device__ __forceinline__ u32x2 dpp_prev(const u32x2 pv, const u32x2 cur) { u32x2 r; r.x = dpp_prev1<N>(pv.x, cur.x); r.y = dpp_prev1<N>(pv.y, cur.y); return r; }
;     static __device__ __forceinline__ u32x2 finish2(const float (&g0)[4], const float (&g1)[4], const float (&g2)[4], const float (&w0)[4], const float (&w1)[4], const float (&w2)[4], const float (&bb)[4],
;                                                     const f32x4 v, float rs) {
;         float h[4];
; #pragma unroll
;         for (int j = 0; j < 4; j += 2) {
;             const f32x2 gc = (f32x2){bb[j] + w0[j] * g2[j] + w1[j] * g1[j] + w2[j] * g0[j], bb[j + 1] + w0[j + 1] * g2[j + 1] + w1[j + 1] * g1[j + 1] + w2[j + 1] * g0[j + 1]};
;             const f32x2 ge = gelu_pk(gc) * ((f32x2){v[j], v[j + 1]} * rs); h[j] = ge.x; h[j + 1] = ge.y; }
;         u32x2 w; w.x = cvt_pk_bf16(h[0], h[1]); w.y = cvt_pk_bf16(h[2], h[3]); return w;
;     __device__ __forceinline__ void operator()(const f32x4 (&acc)[2][2][4][2], const Unit& u, int wr, int wc, int fr, int fq) const {
;     ...
;                 for (int m = 0; m < 4; ++m) { const u32x4 cur = gq[m]; u32x4 hw;
; #pragma unroll
;                     for (int hv = 0; hv < 2; ++hv) { const u32x2 c2 = half2(cur, hv), p2 = half2(pv, hv);
;                         const u32x2 q1 = dpp_prev<1>(p2, c2), q2 = dpp_prev<2>(p2, c2);
;                         float g0[4], g1[4], g2[4]; unpk4(c2, g0); unpk4(q1, g1); unpk4(q2, g2);
;                         const u32x2 r = finish2(g0, g1, g2, w0[hv], w1[hv], w2[hv], bb[hv], acc[ai][bj][m][hv], rs8[ai][m]);
;                         if (hv == 0) { hw.x = r.x; hw.y = r.y; } else { hw.z = r.x; hw.w = r.y; } }
;                     *(u32x4*)(H + (size_t)(R0 + fr + 16 * m) * 2816 + col8) = hw;
	v_pk_fma_f32 v[98:99], v[140:141], v[174:175], v[98:99]
	v_pk_mul_f32 v[92:93], v[92:93], v[128:129] op_sel_hi:[1,0]
	v_pk_mul_f32 v[168:169], v[98:99], s[26:27] op_sel_hi:[1,0]
	v_pk_mul_f32 v[98:99], v[98:99], 0.5 op_sel_hi:[1,0]
	v_med3_f32 v168, v168, s71, v224
	v_med3_f32 v169, v169, s71, v224
	v_pk_mul_f32 v[174:175], v[168:169], v[168:169]
	v_readlane_b32 s0, v240, 58
	v_pk_fma_f32 v[178:179], v[174:175], s[28:29], v[116:117] op_sel_hi:[1,0,0] neg_lo:[1,0,0] neg_hi:[1,0,0]
	v_readlane_b32 s1, v240, 59
	v_pk_fma_f32 v[178:179], v[174:175], v[178:179], s[34:35] op_sel_hi:[1,1,0]
	v_pk_mul_f32 v[94:95], v[94:95], v[128:129] op_sel_hi:[1,0]
	v_pk_fma_f32 v[178:179], v[174:175], v[178:179], s[36:37] op_sel_hi:[1,1,0]
	v_mov_b32_dpp v3, v112 row_ror:1 row_mask:0xf bank_mask:0xf bound_ctrl:1
	v_pk_fma_f32 v[178:179], v[174:175], v[178:179], s[38:39] op_sel_hi:[1,1,0]
	v_pk_mul_f32 v[88:89], v[88:89], v[126:127] op_sel_hi:[1,0]
	v_pk_fma_f32 v[178:179], v[174:175], v[178:179], s[40:41] op_sel_hi:[1,1,0]
	v_mov_b32_dpp v3, v108 row_shr:1 row_mask:0xf bank_mask:0xf
	v_pk_fma_f32 v[178:179], v[174:175], v[178:179], s[42:43] op_sel_hi:[1,1,0]
	v_pk_mul_f32 v[90:91], v[90:91], v[126:127] op_sel_hi:[1,0]
	v_pk_fma_f32 v[174:175], v[174:175], v[178:179], s[44:45] op_sel_hi:[1,1,0]
	v_pk_mul_f32 v[84:85], v[84:85], v[126:127] op_sel_hi:[1,0]
	v_pk_mul_f32 v[168:169], v[168:169], v[174:175]
	v_pk_mul_f32 v[86:87], v[86:87], v[126:127] op_sel_hi:[1,0]
	v_pk_fma_f32 v[98:99], v[98:99], v[168:169], v[98:99]
	v_pk_fma_f32 v[168:169], v[134:135], v[170:171], v[146:147]
	v_pk_mul_f32 v[92:93], v[92:93], v[98:99]
	v_lshlrev_b32_e32 v98, 16, v115
	v_and_b32_e32 v99, 0xffff0000, v115
	v_pk_fma_f32 v[118:119], v[138:139], v[118:119], v[168:169]
	v_pk_mul_f32 v[80:81], v[80:81], v[124:125] op_sel_hi:[1,0]
	v_pk_fma_f32 v[98:99], v[142:143], v[98:99], v[118:119]
	v_pk_mul_f32 v[82:83], v[82:83], v[124:125] op_sel_hi:[1,0]
	v_pk_mul_f32 v[118:119], v[98:99], s[26:27] op_sel_hi:[1,0]
	v_pk_mul_f32 v[98:99], v[98:99], 0.5 op_sel_hi:[1,0]
	v_med3_f32 v118, v118, s71, v224
	v_med3_f32 v119, v119, s71, v224
	v_pk_mul_f32 v[168:169], v[118:119], v[118:119]
	v_pk_mul_f32 v[76:77], v[76:77], v[124:125] op_sel_hi:[1,0]
	v_pk_fma_f32 v[170:171], v[168:169], s[28:29], v[116:117] op_sel_hi:[1,0,0] neg_lo:[1,0,0] neg_hi:[1,0,0]
	v_pk_mul_f32 v[78:79], v[78:79], v[124:125] op_sel_hi:[1,0]
	v_pk_fma_f32 v[170:171], v[168:169], v[170:171], s[34:35] op_sel_hi:[1,1,0]
	v_pk_mul_f32 v[72:73], v[72:73], v[122:123] op_sel_hi:[1,0]
	v_pk_fma_f32 v[170:171], v[168:169], v[170:171], s[36:37] op_sel_hi:[1,1,0]
	v_pk_mul_f32 v[74:75], v[74:75], v[122:123] op_sel_hi:[1,0]
	v_pk_fma_f32 v[170:171], v[168:169], v[170:171], s[38:39] op_sel_hi:[1,1,0]
	v_pk_mul_f32 v[64:65], v[64:65], v[122:123] op_sel_hi:[1,0]
	v_pk_fma_f32 v[170:171], v[168:169], v[170:171], s[40:41] op_sel_hi:[1,1,0]
	v_pk_mul_f32 v[66:67], v[66:67], v[122:123] op_sel_hi:[1,0]
	v_pk_fma_f32 v[170:171], v[168:169], v[170:171], s[42:43] op_sel_hi:[1,1,0]
	s_nop 0
	v_pk_fma_f32 v[168:169], v[168:169], v[170:171], s[44:45] op_sel_hi:[1,1,0]
	s_nop 0
	v_pk_mul_f32 v[118:119], v[118:119], v[168:169]
	v_lshl_add_u64 v[168:169], s[0:1], 0, v[120:121]
	v_pk_fma_f32 v[98:99], v[98:99], v[118:119], v[98:99]
	v_mov_b32_e32 v120, 0
	v_pk_mul_f32 v[94:95], v[94:95], v[98:99]
	v_cvt_pk_bf16_f32 v98, v92, v93
	v_lshl_add_u64 v[92:93], v[168:169], 0, v[180:181]
	v_cvt_pk_bf16_f32 v99, v94, v95
	global_store_dwordx4 v[92:93], v[96:99], off sc1
	v_lshlrev_b32_e32 v92, 16, v3
	v_and_b32_e32 v93, 0xffff0000, v3
	v_mov_b32_dpp v97, v112 row_ror:2 row_mask:0xf bank_mask:0xf bound_ctrl:1
	v_mov_b32_dpp v95, v113 row_ror:1 row_mask:0xf bank_mask:0xf bound_ctrl:1
	v_mov_b32_dpp v99, v113 row_ror:2 row_mask:0xf bank_mask:0xf bound_ctrl:1
	v_mov_b32_dpp v97, v108 row_shr:2 row_mask:0xf bank_mask:0xf
	v_lshlrev_b32_e32 v96, 16, v97
	v_and_b32_e32 v97, 0xffff0000, v97
	v_pk_fma_f32 v[96:97], v[148:149], v[96:97], v[160:161]
	v_lshlrev_b32_e32 v112, 16, v108
	v_and_b32_e32 v113, 0xffff0000, v108
	v_pk_fma_f32 v[92:93], v[152:153], v[92:93], v[96:97]
	v_mov_b32_dpp v99, v109 row_shr:2 row_mask:0xf bank_mask:0xf
	v_pk_fma_f32 v[92:93], v[156:157], v[112:113], v[92:93]
	v_mov_b32_dpp v95, v109 row_shr:1 row_mask:0xf bank_mask:0xf
	v_pk_mul_f32 v[96:97], v[92:93], s[26:27] op_sel_hi:[1,0]
	v_lshlrev_b32_e32 v98, 16, v99
	v_med3_f32 v96, v96, s71, v224
	v_med3_f32 v97, v97, s71, v224
	v_pk_mul_f32 v[112:113], v[96:97], v[96:97]
	v_and_b32_e32 v99, 0xffff0000, v99
	v_pk_fma_f32 v[118:119], v[112:113], s[28:29], v[116:117] op_sel_hi:[1,0,0] neg_lo:[1,0,0] neg_hi:[1,0,0]
	v_pk_mul_f32 v[92:93], v[92:93], 0.5 op_sel_hi:[1,0]
	v_pk_fma_f32 v[118:119], v[112:113], v[118:119], s[34:35] op_sel_hi:[1,1,0]
	v_lshlrev_b32_e32 v94, 16, v95
	v_pk_fma_f32 v[118:119], v[112:113], v[118:119], s[36:37] op_sel_hi:[1,1,0]
	v_and_b32_e32 v95, 0xffff0000, v95
	v_pk_fma_f32 v[118:119], v[112:113], v[118:119], s[38:39] op_sel_hi:[1,1,0]
	v_mov_b32_dpp v3, v114 row_ror:1 row_mask:0xf bank_mask:0xf bound_ctrl:1
	v_pk_fma_f32 v[118:119], v[112:113], v[118:119], s[40:41] op_sel_hi:[1,1,0]
	v_mov_b32_e32 v121, 0
	v_pk_fma_f32 v[118:119], v[112:113], v[118:119], s[42:43] op_sel_hi:[1,1,0]
	v_mov_b32_dpp v3, v110 row_shr:1 row_mask:0xf bank_mask:0xf
	v_pk_fma_f32 v[112:113], v[112:113], v[118:119], s[44:45] op_sel_hi:[1,1,0]
	v_mov_b32_e32 v118, 0
	v_pk_mul_f32 v[96:97], v[96:97], v[112:113]
	v_mov_b32_e32 v119, 0
	v_pk_fma_f32 v[92:93], v[92:93], v[96:97], v[92:93]
	v_pk_fma_f32 v[96:97], v[150:151], v[98:99], v[162:163]
	v_pk_mul_f32 v[88:89], v[88:89], v[92:93]
	v_lshlrev_b32_e32 v92, 16, v109
; __device__ __forceinline__ unsigned cvt_pk_bf16(float lo, float hi) { unsigned r; asm volatile("v_cvt_pk_bf16_f32 %0, %1, %2" : "=v"(r) : "v"(lo), "v"(hi)); return r; }
;     static __device__ __forceinline__ void unpk4(const u32x2 w, float (&o)[4]) { o[0] = bf_lo(w.x); o[1] = bf_hi(w.x); o[2] = bf_lo(w.y); o[3] = bf_hi(w.y); }
;     template <int N> static __device__ __forceinline__ u32x2 dpp_prev(const u32x2 pv, const u32x2 cur) { u32x2 r; r.x = dpp_prev1<N>(pv.x, cur.x); r.y = dpp_prev1<N>(pv.y, cur.y); return r; }
;     static __device__ __forceinline__ u32x2 finish2(const float (&g0)[4], const float (&g1)[4], const float (&g2)[4], const float (&w0)[4], const float (&w1)[4], const float (&w2)[4], const float (&bb)[4],
;                                                     const f32x4 v, float rs) {
;         float h[4];
; #pragma unroll
;         for (int j = 0; j < 4; j += 2) {
;             const f32x2 gc = (f32x2){bb[j] + w0[j] * g2[j] + w1[j] * g1[j] + w2[j] * g0[j], bb[j + 1] + w0[j + 1] * g2[j + 1] + w1[j + 1] * g1[j + 1] + w2[j + 1] * g0[j + 1]};
;             const f32x2 ge = gelu_pk(gc) * ((f32x2){v[j], v[j + 1]} * rs); h[j] = ge.x; h[j + 1] = ge.y; }
;         u32x2 w; w.x = cvt_pk_bf16(h[0], h[1]); w.y = cvt_pk_bf16(h[2], h[3]); return w;
;     __device__ __forceinline__ void operator()(const f32x4 (&acc)[2][2][4][2], const Unit& u, int wr, int wc, int fr, int fq) const {
;     ...
;                 for (int m = 0; m < 4; ++m) { const u32x4 cur = gq[m]; u32x4 hw;
; #pragma unroll
;                     for (int hv = 0; hv < 2; ++hv) { const u32x2 c2 = half2(cur, hv), p2 = half2(pv, hv);
;                         const u32x2 q1 = dpp_prev<1>(p2, c2), q2 = dpp_prev<2>(p2, c2);
;                         float g0[4], g1[4], g2[4]; unpk4(c2, g0); unpk4(q1, g1); unpk4(q2, g2);
;                         const u32x2 r = finish2(g0, g1, g2, w0[hv], w1[hv], w2[hv], bb[hv], acc[ai][bj][m][hv], rs8[ai][m]);
;                         if (hv == 0) { hw.x = r.x; hw.y = r.y; } else { hw.z = r.x; hw.w = r.y; } }
;                     *(u32x4*)(H + (size_t)(R0 + fr + 16 * m) * 2816 + col8) = hw;
	v_and_b32_e32 v93, 0xffff0000, v109
	v_pk_fma_f32 v[94:95], v[154:155], v[94:95], v[96:97]
	v_cvt_pk_bf16_f32 v88, v88, v89
	s_nop 0
	v_pk_fma_f32 v[92:93], v[158:159], v[92:93], v[94:95]
	s_nop 0
	v_pk_mul_f32 v[94:95], v[92:93], s[26:27] op_sel_hi:[1,0]
	v_pk_mul_f32 v[92:93], v[92:93], 0.5 op_sel_hi:[1,0]
	v_med3_f32 v94, v94, s71, v224
	v_med3_f32 v95, v95, s71, v224
	v_pk_mul_f32 v[96:97], v[94:95], v[94:95]
	s_nop 0
	v_pk_fma_f32 v[98:99], v[96:97], s[28:29], v[116:117] op_sel_hi:[1,0,0] neg_lo:[1,0,0] neg_hi:[1,0,0]
	s_nop 0
	v_pk_fma_f32 v[98:99], v[96:97], v[98:99], s[34:35] op_sel_hi:[1,1,0]
	s_nop 0
	v_pk_fma_f32 v[98:99], v[96:97], v[98:99], s[36:37] op_sel_hi:[1,1,0]
	s_nop 0
	v_pk_fma_f32 v[98:99], v[96:97], v[98:99], s[38:39] op_sel_hi:[1,1,0]
	s_nop 0
	v_pk_fma_f32 v[98:99], v[96:97], v[98:99], s[40:41] op_sel_hi:[1,1,0]
	s_nop 0
	v_pk_fma_f32 v[98:99], v[96:97], v[98:99], s[42:43] op_sel_hi:[1,1,0]
	s_nop 0
	v_pk_fma_f32 v[96:97], v[96:97], v[98:99], s[44:45] op_sel_hi:[1,1,0]
	v_lshlrev_b32_e32 v98, 16, v110
	v_pk_mul_f32 v[94:95], v[94:95], v[96:97]
	v_and_b32_e32 v99, 0xffff0000, v110
	v_pk_fma_f32 v[92:93], v[92:93], v[94:95], v[92:93]
	v_mov_b32_dpp v95, v114 row_ror:2 row_mask:0xf bank_mask:0xf bound_ctrl:1
	v_pk_mul_f32 v[90:91], v[90:91], v[92:93]
	v_mov_b32_dpp v97, v115 row_ror:2 row_mask:0xf bank_mask:0xf bound_ctrl:1
	v_mov_b32_dpp v95, v110 row_shr:2 row_mask:0xf bank_mask:0xf
	v_lshlrev_b32_e32 v94, 16, v95
	v_and_b32_e32 v95, 0xffff0000, v95
	v_cvt_pk_bf16_f32 v89, v90, v91
	v_lshlrev_b32_e32 v90, 16, v3
	v_and_b32_e32 v91, 0xffff0000, v3
	v_pk_fma_f32 v[94:95], v[132:133], v[94:95], v[144:145]
	v_mov_b32_dpp v93, v115 row_ror:1 row_mask:0xf bank_mask:0xf bound_ctrl:1
	v_pk_fma_f32 v[90:91], v[136:137], v[90:91], v[94:95]
	v_mov_b32_dpp v97, v111 row_shr:2 row_mask:0xf bank_mask:0xf
	v_pk_fma_f32 v[90:91], v[140:141], v[98:99], v[90:91]
	v_mov_b32_dpp v93, v111 row_shr:1 row_mask:0xf bank_mask:0xf
	v_pk_mul_f32 v[94:95], v[90:91], s[26:27] op_sel_hi:[1,0]
	v_lshlrev_b32_e32 v96, 16, v97
	v_med3_f32 v94, v94, s71, v224
	v_med3_f32 v95, v95, s71, v224
	v_pk_mul_f32 v[98:99], v[94:95], v[94:95]
	v_and_b32_e32 v97, 0xffff0000, v97
	v_pk_fma_f32 v[112:113], v[98:99], s[28:29], v[116:117] op_sel_hi:[1,0,0] neg_lo:[1,0,0] neg_hi:[1,0,0]
	v_pk_mul_f32 v[90:91], v[90:91], 0.5 op_sel_hi:[1,0]
	v_pk_fma_f32 v[112:113], v[98:99], v[112:113], s[34:35] op_sel_hi:[1,1,0]
	v_lshlrev_b32_e32 v92, 16, v93
	v_pk_fma_f32 v[112:113], v[98:99], v[112:113], s[36:37] op_sel_hi:[1,1,0]
	v_and_b32_e32 v93, 0xffff0000, v93
	v_pk_fma_f32 v[112:113], v[98:99], v[112:113], s[38:39] op_sel_hi:[1,1,0]
	v_add_u32_e32 v3, 16, v1
	v_pk_fma_f32 v[112:113], v[98:99], v[112:113], s[40:41] op_sel_hi:[1,1,0]
	s_nop 0
	v_pk_fma_f32 v[112:113], v[98:99], v[112:113], s[42:43] op_sel_hi:[1,1,0]
	s_nop 0
	v_pk_fma_f32 v[98:99], v[98:99], v[112:113], s[44:45] op_sel_hi:[1,1,0]
	s_nop 0
	v_pk_mul_f32 v[94:95], v[94:95], v[98:99]
	s_nop 0
	v_pk_fma_f32 v[90:91], v[90:91], v[94:95], v[90:91]
	v_pk_fma_f32 v[94:95], v[134:135], v[96:97], v[146:147]
	v_pk_mul_f32 v[84:85], v[84:85], v[90:91]
	v_lshlrev_b32_e32 v90, 16, v111
	v_and_b32_e32 v91, 0xffff0000, v111
	v_pk_fma_f32 v[92:93], v[138:139], v[92:93], v[94:95]
	s_nop 0
	v_pk_fma_f32 v[90:91], v[142:143], v[90:91], v[92:93]
	s_nop 0
	v_pk_mul_f32 v[92:93], v[90:91], s[26:27] op_sel_hi:[1,0]
	v_pk_mul_f32 v[90:91], v[90:91], 0.5 op_sel_hi:[1,0]
	v_med3_f32 v92, v92, s71, v224
	v_med3_f32 v93, v93, s71, v224
	v_pk_mul_f32 v[94:95], v[92:93], v[92:93]
	s_nop 0
	v_pk_fma_f32 v[96:97], v[94:95], s[28:29], v[116:117] op_sel_hi:[1,0,0] neg_lo:[1,0,0] neg_hi:[1,0,0]
	s_nop 0
	v_pk_fma_f32 v[96:97], v[94:95], v[96:97], s[34:35] op_sel_hi:[1,1,0]
	s_nop 0
	v_pk_fma_f32 v[96:97], v[94:95], v[96:97], s[36:37] op_sel_hi:[1,1,0]
	s_nop 0
	v_pk_fma_f32 v[96:97], v[94:95], v[96:97], s[38:39] op_sel_hi:[1,1,0]
	s_nop 0
	v_pk_fma_f32 v[96:97], v[94:95], v[96:97], s[40:41] op_sel_hi:[1,1,0]
	s_nop 0
	v_pk_fma_f32 v[96:97], v[94:95], v[96:97], s[42:43] op_sel_hi:[1,1,0]
	s_nop 0
	v_pk_fma_f32 v[94:95], v[94:95], v[96:97], s[44:45] op_sel_hi:[1,1,0]
	s_nop 0
	v_pk_mul_f32 v[92:93], v[92:93], v[94:95]
	v_lshlrev_b32_e32 v94, 16, v104
	v_pk_fma_f32 v[90:91], v[90:91], v[92:93], v[90:91]
	v_and_b32_e32 v95, 0xffff0000, v104
	v_pk_mul_f32 v[86:87], v[86:87], v[90:91]
	v_cvt_pk_bf16_f32 v90, v84, v85
	v_mov_b64_e32 v[84:85], s[0:1]
	v_mad_i64_i32 v[170:171], s[0:1], v3, s67, v[84:85]
	v_cvt_pk_bf16_f32 v91, v86, v87
	v_lshl_add_u64 v[86:87], v[170:171], 0, v[180:181]
	global_store_dwordx4 v[86:87], v[88:91], off sc1
	v_mov_b32_dpp v3, v108 row_ror:1 row_mask:0xf bank_mask:0xf bound_ctrl:1
	v_mov_b32_dpp v93, v109 row_ror:2 row_mask:0xf bank_mask:0xf bound_ctrl:1
	v_mov_b32_dpp v91, v108 row_ror:2 row_mask:0xf bank_mask:0xf bound_ctrl:1
	v_mov_b32_dpp v3, v104 row_shr:1 row_mask:0xf bank_mask:0xf
	v_lshlrev_b32_e32 v86, 16, v3
	v_mov_b32_dpp v91, v104 row_shr:2 row_mask:0xf bank_mask:0xf
	v_lshlrev_b32_e32 v90, 16, v91
	v_and_b32_e32 v91, 0xffff0000, v91
	v_and_b32_e32 v87, 0xffff0000, v3
	v_pk_fma_f32 v[90:91], v[148:149], v[90:91], v[160:161]
	v_mov_b32_dpp v89, v109 row_ror:1 row_mask:0xf bank_mask:0xf bound_ctrl:1
	v_pk_fma_f32 v[86:87], v[152:153], v[86:87], v[90:91]
	v_mov_b32_dpp v93, v105 row_shr:2 row_mask:0xf bank_mask:0xf
	v_pk_fma_f32 v[86:87], v[156:157], v[94:95], v[86:87]
	v_mov_b32_dpp v89, v105 row_shr:1 row_mask:0xf bank_mask:0xf
	v_pk_mul_f32 v[90:91], v[86:87], s[26:27] op_sel_hi:[1,0]
	v_lshlrev_b32_e32 v92, 16, v93
	v_med3_f32 v90, v90, s71, v224
	v_med3_f32 v91, v91, s71, v224
	v_pk_mul_f32 v[94:95], v[90:91], v[90:91]
; __device__ __forceinline__ unsigned cvt_pk_bf16(float lo, float hi) { unsigned r; asm volatile("v_cvt_pk_bf16_f32 %0, %1, %2" : "=v"(r) : "v"(lo), "v"(hi)); return r; }
;     static __device__ __forceinline__ void unpk4(const u32x2 w, float (&o)[4]) { o[0] = bf_lo(w.x); o[1] = bf_hi(w.x); o[2] = bf_lo(w.y); o[3] = bf_hi(w.y); }
;     template <int N> static __device__ __forceinline__ u32x2 dpp_prev(const u32x2 pv, const u32x2 cur) { u32x2 r; r.x = dpp_prev1<N>(pv.x, cur.x); r.y = dpp_prev1<N>(pv.y, cur.y); return r; }
;     static __device__ __forceinline__ u32x2 finish2(const float (&g0)[4], const float (&g1)[4], const float (&g2)[4], const float (&w0)[4], const float (&w1)[4], const float (&w2)[4], const float (&bb)[4],
;                                                     const f32x4 v, float rs) {
;         float h[4];
; #pragma unroll
;         for (int j = 0; j < 4; j += 2) {
;             const f32x2 gc = (f32x2){bb[j] + w0[j] * g2[j] + w1[j] * g1[j] + w2[j] * g0[j], bb[j + 1] + w0[j + 1] * g2[j + 1] + w1[j + 1] * g1[j + 1] + w2[j + 1] * g0[j + 1]};
;             const f32x2 ge = gelu_pk(gc) * ((f32x2){v[j], v[j + 1]} * rs); h[j] = ge.x; h[j + 1] = ge.y; }
;         u32x2 w; w.x = cvt_pk_bf16(h[0], h[1]); w.y = cvt_pk_bf16(h[2], h[3]); return w;
;     __device__ __forceinline__ void operator()(const f32x4 (&acc)[2][2][4][2], const Unit& u, int wr, int wc, int fr, int fq) const {
;     ...
;                 for (int m = 0; m < 4; ++m) { const u32x4 cur = gq[m]; u32x4 hw;
; #pragma unroll
;                     for (int hv = 0; hv < 2; ++hv) { const u32x2 c2 = half2(cur, hv), p2 = half2(pv, hv);
;                         const u32x2 q1 = dpp_prev<1>(p2, c2), q2 = dpp_prev<2>(p2, c2);
;                         float g0[4], g1[4], g2[4]; unpk4(c2, g0); unpk4(q1, g1); unpk4(q2, g2);
;                         const u32x2 r = finish2(g0, g1, g2, w0[hv], w1[hv], w2[hv], bb[hv], acc[ai][bj][m][hv], rs8[ai][m]);
;                         if (hv == 0) { hw.x = r.x; hw.y = r.y; } else { hw.z = r.x; hw.w = r.y; } }
;                     *(u32x4*)(H + (size_t)(R0 + fr + 16 * m) * 2816 + col8) = hw;
	v_and_b32_e32 v93, 0xffff0000, v93
	v_pk_fma_f32 v[96:97], v[94:95], s[28:29], v[116:117] op_sel_hi:[1,0,0] neg_lo:[1,0,0] neg_hi:[1,0,0]
	v_pk_mul_f32 v[86:87], v[86:87], 0.5 op_sel_hi:[1,0]
	v_pk_fma_f32 v[96:97], v[94:95], v[96:97], s[34:35] op_sel_hi:[1,1,0]
	v_lshlrev_b32_e32 v88, 16, v89
	v_pk_fma_f32 v[96:97], v[94:95], v[96:97], s[36:37] op_sel_hi:[1,1,0]
	v_and_b32_e32 v89, 0xffff0000, v89
	v_pk_fma_f32 v[96:97], v[94:95], v[96:97], s[38:39] op_sel_hi:[1,1,0]
	v_mov_b32_dpp v3, v110 row_ror:1 row_mask:0xf bank_mask:0xf bound_ctrl:1
	v_pk_fma_f32 v[96:97], v[94:95], v[96:97], s[40:41] op_sel_hi:[1,1,0]
	s_nop 0
	v_pk_fma_f32 v[96:97], v[94:95], v[96:97], s[42:43] op_sel_hi:[1,1,0]
	v_mov_b32_dpp v3, v106 row_shr:1 row_mask:0xf bank_mask:0xf
	v_pk_fma_f32 v[94:95], v[94:95], v[96:97], s[44:45] op_sel_hi:[1,1,0]
	s_nop 0
	v_pk_mul_f32 v[90:91], v[90:91], v[94:95]
	s_nop 0
	v_pk_fma_f32 v[86:87], v[86:87], v[90:91], v[86:87]
	v_pk_fma_f32 v[90:91], v[150:151], v[92:93], v[162:163]
	v_pk_mul_f32 v[80:81], v[80:81], v[86:87]
	v_lshlrev_b32_e32 v86, 16, v105
	v_and_b32_e32 v87, 0xffff0000, v105
	v_pk_fma_f32 v[88:89], v[154:155], v[88:89], v[90:91]
	v_cvt_pk_bf16_f32 v80, v80, v81
	s_nop 0
	v_pk_fma_f32 v[86:87], v[158:159], v[86:87], v[88:89]
	s_nop 0
	v_pk_mul_f32 v[88:89], v[86:87], s[26:27] op_sel_hi:[1,0]
	v_pk_mul_f32 v[86:87], v[86:87], 0.5 op_sel_hi:[1,0]
	v_med3_f32 v88, v88, s71, v224
	v_med3_f32 v89, v89, s71, v224
	v_pk_mul_f32 v[90:91], v[88:89], v[88:89]
	s_nop 0
	v_pk_fma_f32 v[92:93], v[90:91], s[28:29], v[116:117] op_sel_hi:[1,0,0] neg_lo:[1,0,0] neg_hi:[1,0,0]
	s_nop 0
	v_pk_fma_f32 v[92:93], v[90:91], v[92:93], s[34:35] op_sel_hi:[1,1,0]
	s_nop 0
	v_pk_fma_f32 v[92:93], v[90:91], v[92:93], s[36:37] op_sel_hi:[1,1,0]
	s_nop 0
	v_pk_fma_f32 v[92:93], v[90:91], v[92:93], s[38:39] op_sel_hi:[1,1,0]
	s_nop 0
	v_pk_fma_f32 v[92:93], v[90:91], v[92:93], s[40:41] op_sel_hi:[1,1,0]
	s_nop 0
	v_pk_fma_f32 v[92:93], v[90:91], v[92:93], s[42:43] op_sel_hi:[1,1,0]
	s_nop 0
	v_pk_fma_f32 v[90:91], v[90:91], v[92:93], s[44:45] op_sel_hi:[1,1,0]
	v_lshlrev_b32_e32 v92, 16, v106
	v_pk_mul_f32 v[88:89], v[88:89], v[90:91]
	v_and_b32_e32 v93, 0xffff0000, v106
	v_pk_fma_f32 v[86:87], v[86:87], v[88:89], v[86:87]
	v_mov_b32_dpp v89, v110 row_ror:2 row_mask:0xf bank_mask:0xf bound_ctrl:1
	v_pk_mul_f32 v[82:83], v[82:83], v[86:87]
	v_mov_b32_dpp v91, v111 row_ror:2 row_mask:0xf bank_mask:0xf bound_ctrl:1
	v_mov_b32_dpp v89, v106 row_shr:2 row_mask:0xf bank_mask:0xf
	v_lshlrev_b32_e32 v88, 16, v89
	v_and_b32_e32 v89, 0xffff0000, v89
	v_cvt_pk_bf16_f32 v81, v82, v83
	v_lshlrev_b32_e32 v82, 16, v3
	v_and_b32_e32 v83, 0xffff0000, v3
	v_pk_fma_f32 v[88:89], v[132:133], v[88:89], v[144:145]
	v_mov_b32_dpp v87, v111 row_ror:1 row_mask:0xf bank_mask:0xf bound_ctrl:1
	v_pk_fma_f32 v[82:83], v[136:137], v[82:83], v[88:89]
	v_mov_b32_dpp v91, v107 row_shr:2 row_mask:0xf bank_mask:0xf
	v_pk_fma_f32 v[82:83], v[140:141], v[92:93], v[82:83]
	v_mov_b32_dpp v87, v107 row_shr:1 row_mask:0xf bank_mask:0xf
	v_pk_mul_f32 v[88:89], v[82:83], s[26:27] op_sel_hi:[1,0]
	v_lshlrev_b32_e32 v90, 16, v91
	v_med3_f32 v88, v88, s71, v224
	v_med3_f32 v89, v89, s71, v224
	v_pk_mul_f32 v[92:93], v[88:89], v[88:89]
	v_and_b32_e32 v91, 0xffff0000, v91
	v_pk_fma_f32 v[94:95], v[92:93], s[28:29], v[116:117] op_sel_hi:[1,0,0] neg_lo:[1,0,0] neg_hi:[1,0,0]
	v_pk_mul_f32 v[82:83], v[82:83], 0.5 op_sel_hi:[1,0]
	v_pk_fma_f32 v[94:95], v[92:93], v[94:95], s[34:35] op_sel_hi:[1,1,0]
	v_lshlrev_b32_e32 v86, 16, v87
	v_pk_fma_f32 v[94:95], v[92:93], v[94:95], s[36:37] op_sel_hi:[1,1,0]
	v_and_b32_e32 v87, 0xffff0000, v87
	v_pk_fma_f32 v[94:95], v[92:93], v[94:95], s[38:39] op_sel_hi:[1,1,0]
	v_add_u32_e32 v3, 32, v1
	v_pk_fma_f32 v[94:95], v[92:93], v[94:95], s[40:41] op_sel_hi:[1,1,0]
	v_mad_i64_i32 v[174:175], s[0:1], v3, s67, v[84:85]
	v_pk_fma_f32 v[94:95], v[92:93], v[94:95], s[42:43] op_sel_hi:[1,1,0]
	v_mov_b32_dpp v3, v104 row_ror:1 row_mask:0xf bank_mask:0xf bound_ctrl:1
	v_pk_fma_f32 v[92:93], v[92:93], v[94:95], s[44:45] op_sel_hi:[1,1,0]
	v_add_u32_e32 v1, 48, v1
	v_pk_mul_f32 v[88:89], v[88:89], v[92:93]
	v_mov_b32_dpp v3, v100 row_shr:1 row_mask:0xf bank_mask:0xf
	v_pk_fma_f32 v[82:83], v[82:83], v[88:89], v[82:83]
	v_pk_fma_f32 v[88:89], v[134:135], v[90:91], v[146:147]
	v_pk_mul_f32 v[76:77], v[76:77], v[82:83]
	v_lshlrev_b32_e32 v82, 16, v107
	v_and_b32_e32 v83, 0xffff0000, v107
	v_pk_fma_f32 v[86:87], v[138:139], v[86:87], v[88:89]
	s_nop 0
	v_pk_fma_f32 v[82:83], v[142:143], v[82:83], v[86:87]
	s_nop 0
	v_pk_mul_f32 v[86:87], v[82:83], s[26:27] op_sel_hi:[1,0]
	v_pk_mul_f32 v[82:83], v[82:83], 0.5 op_sel_hi:[1,0]
	v_med3_f32 v86, v86, s71, v224
	v_med3_f32 v87, v87, s71, v224
	v_pk_mul_f32 v[88:89], v[86:87], v[86:87]
	s_nop 0
	v_pk_fma_f32 v[90:91], v[88:89], s[28:29], v[116:117] op_sel_hi:[1,0,0] neg_lo:[1,0,0] neg_hi:[1,0,0]
	s_nop 0
	v_pk_fma_f32 v[90:91], v[88:89], v[90:91], s[34:35] op_sel_hi:[1,1,0]
	s_nop 0
	v_pk_fma_f32 v[90:91], v[88:89], v[90:91], s[36:37] op_sel_hi:[1,1,0]
	s_nop 0
	v_pk_fma_f32 v[90:91], v[88:89], v[90:91], s[38:39] op_sel_hi:[1,1,0]
	s_nop 0
	v_pk_fma_f32 v[90:91], v[88:89], v[90:91], s[40:41] op_sel_hi:[1,1,0]
	s_nop 0
	v_pk_fma_f32 v[90:91], v[88:89], v[90:91], s[42:43] op_sel_hi:[1,1,0]
	s_nop 0
	v_pk_fma_f32 v[88:89], v[88:89], v[90:91], s[44:45] op_sel_hi:[1,1,0]
	s_nop 0
	v_pk_mul_f32 v[86:87], v[86:87], v[88:89]
	s_nop 0
	v_pk_fma_f32 v[82:83], v[82:83], v[86:87], v[82:83]
	v_lshlrev_b32_e32 v86, 16, v100
	v_pk_mul_f32 v[78:79], v[78:79], v[82:83]
	v_cvt_pk_bf16_f32 v82, v76, v77
	v_lshl_add_u64 v[76:77], v[174:175], 0, v[180:181]
; __device__ __forceinline__ unsigned cvt_pk_bf16(float lo, float hi) { unsigned r; asm volatile("v_cvt_pk_bf16_f32 %0, %1, %2" : "=v"(r) : "v"(lo), "v"(hi)); return r; }
;     static __device__ __forceinline__ void unpk4(const u32x2 w, float (&o)[4]) { o[0] = bf_lo(w.x); o[1] = bf_hi(w.x); o[2] = bf_lo(w.y); o[3] = bf_hi(w.y); }
;     template <int N> static __device__ __forceinline__ u32x2 dpp_prev(const u32x2 pv, const u32x2 cur) { u32x2 r; r.x = dpp_prev1<N>(pv.x, cur.x); r.y = dpp_prev1<N>(pv.y, cur.y); return r; }
;     static __device__ __forceinline__ u32x2 finish2(const float (&g0)[4], const float (&g1)[4], const float (&g2)[4], const float (&w0)[4], const float (&w1)[4], const float (&w2)[4], const float (&bb)[4],
;                                                     const f32x4 v, float rs) {
;         float h[4];
; #pragma unroll
;         for (int j = 0; j < 4; j += 2) {
;             const f32x2 gc = (f32x2){bb[j] + w0[j] * g2[j] + w1[j] * g1[j] + w2[j] * g0[j], bb[j + 1] + w0[j + 1] * g2[j + 1] + w1[j + 1] * g1[j + 1] + w2[j + 1] * g0[j + 1]};
;             const f32x2 ge = gelu_pk(gc) * ((f32x2){v[j], v[j + 1]} * rs); h[j] = ge.x; h[j + 1] = ge.y; }
;         u32x2 w; w.x = cvt_pk_bf16(h[0], h[1]); w.y = cvt_pk_bf16(h[2], h[3]); return w;
;     __device__ __forceinline__ void operator()(const f32x4 (&acc)[2][2][4][2], const Unit& u, int wr, int wc, int fr, int fq) const {
;     ...
;                 for (int m = 0; m < 4; ++m) { const u32x4 cur = gq[m]; u32x4 hw;
; #pragma unroll
;                     for (int hv = 0; hv < 2; ++hv) { const u32x2 c2 = half2(cur, hv), p2 = half2(pv, hv);
;                         const u32x2 q1 = dpp_prev<1>(p2, c2), q2 = dpp_prev<2>(p2, c2);
;                         float g0[4], g1[4], g2[4]; unpk4(c2, g0); unpk4(q1, g1); unpk4(q2, g2);
;                         const u32x2 r = finish2(g0, g1, g2, w0[hv], w1[hv], w2[hv], bb[hv], acc[ai][bj][m][hv], rs8[ai][m]);
;                         if (hv == 0) { hw.x = r.x; hw.y = r.y; } else { hw.z = r.x; hw.w = r.y; } }
;                     *(u32x4*)(H + (size_t)(R0 + fr + 16 * m) * 2816 + col8) = hw;
	v_cvt_pk_bf16_f32 v83, v78, v79
	global_store_dwordx4 v[76:77], v[80:83], off sc1
	v_lshlrev_b32_e32 v76, 16, v3
	v_and_b32_e32 v77, 0xffff0000, v3
	v_mov_b32_dpp v81, v104 row_ror:2 row_mask:0xf bank_mask:0xf bound_ctrl:1
	v_and_b32_e32 v87, 0xffff0000, v100
	v_mov_b32_dpp v83, v105 row_ror:2 row_mask:0xf bank_mask:0xf bound_ctrl:1
	v_mov_b32_dpp v81, v100 row_shr:2 row_mask:0xf bank_mask:0xf
	v_lshlrev_b32_e32 v80, 16, v81
	v_and_b32_e32 v81, 0xffff0000, v81
	v_pk_fma_f32 v[80:81], v[148:149], v[80:81], v[160:161]
	v_mov_b32_dpp v79, v105 row_ror:1 row_mask:0xf bank_mask:0xf bound_ctrl:1
	v_pk_fma_f32 v[76:77], v[152:153], v[76:77], v[80:81]
	v_mov_b32_dpp v83, v101 row_shr:2 row_mask:0xf bank_mask:0xf
	v_pk_fma_f32 v[76:77], v[156:157], v[86:87], v[76:77]
	v_mov_b32_dpp v79, v101 row_shr:1 row_mask:0xf bank_mask:0xf
	v_pk_mul_f32 v[80:81], v[76:77], s[26:27] op_sel_hi:[1,0]
	v_lshlrev_b32_e32 v82, 16, v83
	v_med3_f32 v80, v80, s71, v224
	v_med3_f32 v81, v81, s71, v224
	v_pk_mul_f32 v[86:87], v[80:81], v[80:81]
	v_and_b32_e32 v83, 0xffff0000, v83
	v_pk_fma_f32 v[88:89], v[86:87], s[28:29], v[116:117] op_sel_hi:[1,0,0] neg_lo:[1,0,0] neg_hi:[1,0,0]
	v_pk_mul_f32 v[76:77], v[76:77], 0.5 op_sel_hi:[1,0]
	v_pk_fma_f32 v[88:89], v[86:87], v[88:89], s[34:35] op_sel_hi:[1,1,0]
	v_lshlrev_b32_e32 v78, 16, v79
	v_pk_fma_f32 v[88:89], v[86:87], v[88:89], s[36:37] op_sel_hi:[1,1,0]
	v_and_b32_e32 v79, 0xffff0000, v79
	v_pk_fma_f32 v[88:89], v[86:87], v[88:89], s[38:39] op_sel_hi:[1,1,0]
	v_mov_b32_dpp v3, v106 row_ror:1 row_mask:0xf bank_mask:0xf bound_ctrl:1
	v_pk_fma_f32 v[88:89], v[86:87], v[88:89], s[40:41] op_sel_hi:[1,1,0]
	s_nop 0
	v_pk_fma_f32 v[88:89], v[86:87], v[88:89], s[42:43] op_sel_hi:[1,1,0]
	v_mov_b32_dpp v3, v102 row_shr:1 row_mask:0xf bank_mask:0xf
	v_pk_fma_f32 v[86:87], v[86:87], v[88:89], s[44:45] op_sel_hi:[1,1,0]
	s_nop 0
	v_pk_mul_f32 v[80:81], v[80:81], v[86:87]
	s_nop 0
	v_pk_fma_f32 v[76:77], v[76:77], v[80:81], v[76:77]
	v_pk_fma_f32 v[80:81], v[150:151], v[82:83], v[162:163]
	v_pk_mul_f32 v[72:73], v[72:73], v[76:77]
	v_lshlrev_b32_e32 v76, 16, v101
	v_and_b32_e32 v77, 0xffff0000, v101
	v_pk_fma_f32 v[78:79], v[154:155], v[78:79], v[80:81]
	v_cvt_pk_bf16_f32 v72, v72, v73
	s_nop 0
	v_pk_fma_f32 v[76:77], v[158:159], v[76:77], v[78:79]
	s_nop 0
	v_pk_mul_f32 v[78:79], v[76:77], s[26:27] op_sel_hi:[1,0]
	v_pk_mul_f32 v[76:77], v[76:77], 0.5 op_sel_hi:[1,0]
	v_med3_f32 v78, v78, s71, v224
	v_med3_f32 v79, v79, s71, v224
	v_pk_mul_f32 v[80:81], v[78:79], v[78:79]
	s_nop 0
	v_pk_fma_f32 v[82:83], v[80:81], s[28:29], v[116:117] op_sel_hi:[1,0,0] neg_lo:[1,0,0] neg_hi:[1,0,0]
	s_nop 0
	v_pk_fma_f32 v[82:83], v[80:81], v[82:83], s[34:35] op_sel_hi:[1,1,0]
	s_nop 0
	v_pk_fma_f32 v[82:83], v[80:81], v[82:83], s[36:37] op_sel_hi:[1,1,0]
	s_nop 0
	v_pk_fma_f32 v[82:83], v[80:81], v[82:83], s[38:39] op_sel_hi:[1,1,0]
	s_nop 0
	v_pk_fma_f32 v[82:83], v[80:81], v[82:83], s[40:41] op_sel_hi:[1,1,0]
	s_nop 0
	v_pk_fma_f32 v[82:83], v[80:81], v[82:83], s[42:43] op_sel_hi:[1,1,0]
	s_nop 0
	v_pk_fma_f32 v[80:81], v[80:81], v[82:83], s[44:45] op_sel_hi:[1,1,0]
	v_lshlrev_b32_e32 v82, 16, v102
	v_pk_mul_f32 v[78:79], v[78:79], v[80:81]
	v_and_b32_e32 v83, 0xffff0000, v102
	v_pk_fma_f32 v[76:77], v[76:77], v[78:79], v[76:77]
	v_mov_b32_dpp v79, v106 row_ror:2 row_mask:0xf bank_mask:0xf bound_ctrl:1
	v_pk_mul_f32 v[74:75], v[74:75], v[76:77]
	v_mov_b32_dpp v81, v107 row_ror:2 row_mask:0xf bank_mask:0xf bound_ctrl:1
	v_mov_b32_dpp v79, v102 row_shr:2 row_mask:0xf bank_mask:0xf
	v_lshlrev_b32_e32 v78, 16, v79
	v_and_b32_e32 v79, 0xffff0000, v79
	v_cvt_pk_bf16_f32 v73, v74, v75
	v_lshlrev_b32_e32 v74, 16, v3
	v_and_b32_e32 v75, 0xffff0000, v3
	v_pk_fma_f32 v[78:79], v[132:133], v[78:79], v[144:145]
	v_mov_b32_dpp v77, v107 row_ror:1 row_mask:0xf bank_mask:0xf bound_ctrl:1
	v_pk_fma_f32 v[74:75], v[136:137], v[74:75], v[78:79]
	v_mov_b32_dpp v81, v103 row_shr:2 row_mask:0xf bank_mask:0xf
	v_pk_fma_f32 v[74:75], v[140:141], v[82:83], v[74:75]
	v_mov_b32_dpp v77, v103 row_shr:1 row_mask:0xf bank_mask:0xf
	v_pk_mul_f32 v[78:79], v[74:75], s[26:27] op_sel_hi:[1,0]
	v_lshlrev_b32_e32 v80, 16, v81
	v_med3_f32 v78, v78, s71, v224
	v_med3_f32 v79, v79, s71, v224
	v_pk_mul_f32 v[82:83], v[78:79], v[78:79]
	v_and_b32_e32 v81, 0xffff0000, v81
	v_pk_fma_f32 v[86:87], v[82:83], s[28:29], v[116:117] op_sel_hi:[1,0,0] neg_lo:[1,0,0] neg_hi:[1,0,0]
	v_pk_mul_f32 v[74:75], v[74:75], 0.5 op_sel_hi:[1,0]
	v_pk_fma_f32 v[86:87], v[82:83], v[86:87], s[34:35] op_sel_hi:[1,1,0]
	v_lshlrev_b32_e32 v76, 16, v77
	v_pk_fma_f32 v[86:87], v[82:83], v[86:87], s[36:37] op_sel_hi:[1,1,0]
	v_and_b32_e32 v77, 0xffff0000, v77
	v_pk_fma_f32 v[86:87], v[82:83], v[86:87], s[38:39] op_sel_hi:[1,1,0]
	v_mad_i64_i32 v[132:133], s[0:1], v1, s67, v[84:85]
	v_pk_fma_f32 v[86:87], v[82:83], v[86:87], s[40:41] op_sel_hi:[1,1,0]
	s_nop 0
	v_pk_fma_f32 v[86:87], v[82:83], v[86:87], s[42:43] op_sel_hi:[1,1,0]
	s_nop 0
	v_pk_fma_f32 v[82:83], v[82:83], v[86:87], s[44:45] op_sel_hi:[1,1,0]
	s_nop 0
	v_pk_mul_f32 v[78:79], v[78:79], v[82:83]
	s_nop 0
	v_pk_fma_f32 v[74:75], v[74:75], v[78:79], v[74:75]
	v_pk_fma_f32 v[78:79], v[134:135], v[80:81], v[146:147]
	v_pk_mul_f32 v[64:65], v[64:65], v[74:75]
	v_lshlrev_b32_e32 v74, 16, v103
	v_and_b32_e32 v75, 0xffff0000, v103
	v_pk_fma_f32 v[76:77], v[138:139], v[76:77], v[78:79]
	v_add_u32_e32 v134, 0x80, v212
	v_pk_fma_f32 v[74:75], v[142:143], v[74:75], v[76:77]
	v_ashrrev_i32_e32 v135, 31, v134
	v_pk_mul_f32 v[76:77], v[74:75], s[26:27] op_sel_hi:[1,0]
	v_pk_mul_f32 v[74:75], v[74:75], 0.5 op_sel_hi:[1,0]
	v_med3_f32 v76, v76, s71, v224
;     static __device__ __forceinline__ void unpk4(const u32x2 w, float (&o)[4]) { o[0] = bf_lo(w.x); o[1] = bf_hi(w.x); o[2] = bf_lo(w.y); o[3] = bf_hi(w.y); }
;     template <int N> static __device__ __forceinline__ u32x2 dpp_prev(const u32x2 pv, const u32x2 cur) { u32x2 r; r.x = dpp_prev1<N>(pv.x, cur.x); r.y = dpp_prev1<N>(pv.y, cur.y); return r; }
;     __device__ __forceinline__ void operator()(const f32x4 (&acc)[2][2][4][2], const Unit& u, int wr, int wc, int fr, int fq) const {
;     ...
;           for (int bj = 0; bj < 2; ++bj) {
;             const int col8 = u.pn * BM + bj * HALF + wc * 32 + 8 * fq;
;             float w0[2][4], w1[2][4], w2[2][4], bb[2][4];
; #pragma unroll
;             for (int hv = 0; hv < 2; ++hv) { ld4f(cw + col8 + 4 * hv, w0[hv]); ld4f(cw + 2816 + col8 + 4 * hv, w1[hv]); ld4f(cw + 2 * 2816 + col8 + 4 * hv, w2[hv]); ld4f(cb + col8 + 4 * hv, bb[hv]); }
; #pragma unroll
;             for (int ai = 0; ai < 2; ++ai) { const int R0 = u.rb + ai * HALF + wr * 64; const bf16_t* gp = G + (size_t)(R0 + fr) * 2816 + col8;
;                 u32x4 gq[4], prv = (u32x4){0u, 0u, 0u, 0u};
; #pragma unroll
;                 for (int m = 0; m < 4; ++m) gq[m] = *(const u32x4*)(gp + (size_t)m * 16 * 2816);
;                 if ((R0 & 8191) != 0) prv = *(const u32x4*)(gp - (size_t)16 * 2816);
;                 u32x4 pv = prv;
; #pragma unroll
;                 for (int m = 0; m < 4; ++m) { const u32x4 cur = gq[m]; u32x4 hw;
; #pragma unroll
;                     for (int hv = 0; hv < 2; ++hv) { const u32x2 c2 = half2(cur, hv), p2 = half2(pv, hv);
;                         const u32x2 q1 = dpp_prev<1>(p2, c2), q2 = dpp_prev<2>(p2, c2);
;                         float g0[4], g1[4], g2[4]; unpk4(c2, g0); unpk4(q1, g1); unpk4(q2, g2);
;                         const u32x2 r = finish2(g0, g1, g2, w0[hv], w1[hv], w2[hv], bb[hv], acc[ai][bj][m][hv], rs8[ai][m]);
;                         if (hv == 0) { hw.x = r.x; hw.y = r.y; } else { hw.z = r.x; hw.w = r.y; } }
;                     *(u32x4*)(H + (size_t)(R0 + fr + 16 * m) * 2816 + col8) = hw;
	v_med3_f32 v77, v77, s71, v224
	v_pk_mul_f32 v[78:79], v[76:77], v[76:77]
	v_lshl_add_u64 v[136:137], v[134:135], 1, v[214:215]
	v_pk_fma_f32 v[80:81], v[78:79], s[28:29], v[116:117] op_sel_hi:[1,0,0] neg_lo:[1,0,0] neg_hi:[1,0,0]
	v_add_co_u32_e32 v100, vcc, s45, v136
	v_pk_fma_f32 v[80:81], v[78:79], v[80:81], s[34:35] op_sel_hi:[1,1,0]
	s_nop 0
	v_addc_co_u32_e32 v101, vcc, 0, v137, vcc
	v_pk_fma_f32 v[80:81], v[78:79], v[80:81], s[36:37] op_sel_hi:[1,1,0]
	v_add_co_u32_e32 v102, vcc, 0x2c000, v136
	v_pk_fma_f32 v[80:81], v[78:79], v[80:81], s[38:39] op_sel_hi:[1,1,0]
	s_nop 0
	v_addc_co_u32_e32 v103, vcc, 0, v137, vcc
	v_pk_fma_f32 v[80:81], v[78:79], v[80:81], s[40:41] op_sel_hi:[1,1,0]
	s_nop 0
	v_pk_fma_f32 v[80:81], v[78:79], v[80:81], s[42:43] op_sel_hi:[1,1,0]
	s_nop 0
	v_pk_fma_f32 v[78:79], v[78:79], v[80:81], s[44:45] op_sel_hi:[1,1,0]
	s_nop 0
	v_pk_mul_f32 v[76:77], v[76:77], v[78:79]
	s_nop 0
	v_pk_fma_f32 v[74:75], v[74:75], v[76:77], v[74:75]
	s_nop 0
	v_pk_mul_f32 v[66:67], v[66:67], v[74:75]
	v_cvt_pk_bf16_f32 v74, v64, v65
	v_lshl_add_u64 v[64:65], v[132:133], 0, v[180:181]
	v_cvt_pk_bf16_f32 v75, v66, v67
	global_store_dwordx4 v[64:65], v[72:75], off sc1
	v_lshlrev_b64 v[64:65], 2, v[134:135]
	v_lshl_add_u64 v[76:77], s[18:19], 0, v[64:65]
	v_lshl_add_u64 v[72:73], s[12:13], 0, v[64:65]
	v_lshl_add_u64 v[80:81], s[20:21], 0, v[64:65]
	v_lshl_add_u64 v[96:97], s[14:15], 0, v[64:65]
	global_load_dwordx4 v[64:67], v[72:73], off offset:16
	global_load_dwordx4 v[84:87], v[72:73], off
	s_nop 0
	global_load_dwordx4 v[72:75], v[76:77], off offset:16
	global_load_dwordx4 v[88:91], v[76:77], off
	s_nop 0
	global_load_dwordx4 v[76:79], v[80:81], off offset:16
	global_load_dwordx4 v[92:95], v[80:81], off
	s_nop 0
	global_load_dwordx4 v[80:83], v[96:97], off offset:16
	s_nop 0
	global_load_dwordx4 v[96:99], v[96:97], off
	s_nop 0
	global_load_dwordx4 v[114:117], v[136:137], off
	global_load_dwordx4 v[110:113], v[100:101], off
	global_load_dwordx4 v[106:109], v[102:103], off
	v_add_co_u32_e32 v100, vcc, 0x42000, v136
	s_nop 1
	v_addc_co_u32_e32 v101, vcc, 0, v137, vcc
	global_load_dwordx4 v[102:105], v[100:101], off
	v_mov_b32_e32 v100, 0
	s_andn2_b64 vcc, exec, s[2:3]
	s_cbranch_vccnz .LBB0_3150
	v_add_co_u32_e32 v118, vcc, 0xfffea000, v136
	s_nop 1
	v_addc_co_u32_e32 v119, vcc, -1, v137, vcc
	global_load_dwordx4 v[118:121], v[118:119], off
.LBB0_3150:
	s_waitcnt vmcnt(0)
	s_nop 0
	v_mov_b32_dpp v123, v118 row_ror:2 row_mask:0xf bank_mask:0xf bound_ctrl:1
	v_mov_b32_dpp v1, v118 row_ror:1 row_mask:0xf bank_mask:0xf bound_ctrl:1
	v_mov_b32_dpp v101, v119 row_ror:1 row_mask:0xf bank_mask:0xf bound_ctrl:1
	v_mov_b32_dpp v123, v114 row_shr:2 row_mask:0xf bank_mask:0xf
	v_mov_b32_dpp v1, v114 row_shr:1 row_mask:0xf bank_mask:0xf
	v_lshlrev_b32_e32 v138, 16, v123
	v_and_b32_e32 v139, 0xffff0000, v123
	v_mov_b32_dpp v125, v119 row_ror:2 row_mask:0xf bank_mask:0xf bound_ctrl:1
	v_lshlrev_b32_e32 v118, 16, v1
	v_and_b32_e32 v119, 0xffff0000, v1
	v_pk_fma_f32 v[138:139], v[84:85], v[138:139], v[96:97]
	v_lshlrev_b32_e32 v142, 16, v114
	v_and_b32_e32 v143, 0xffff0000, v114
	v_pk_fma_f32 v[118:119], v[88:89], v[118:119], v[138:139]
	v_mov_b32_dpp v125, v115 row_shr:2 row_mask:0xf bank_mask:0xf
	v_pk_fma_f32 v[138:139], v[92:93], v[142:143], v[118:119]
	v_mov_b32_e32 v189, v188
	v_pk_mul_f32 v[118:119], v[138:139], s[26:27] op_sel_hi:[1,0]
	v_mov_b32_dpp v101, v115 row_shr:1 row_mask:0xf bank_mask:0xf
	v_med3_f32 v142, v118, s71, v224
	v_med3_f32 v143, v119, s71, v224
	v_pk_mul_f32 v[144:145], v[142:143], v[142:143]
	v_mov_b64_e32 v[118:119], s[30:31]
	v_pk_fma_f32 v[146:147], v[144:145], s[28:29], v[118:119] op_sel_hi:[1,0,0] neg_lo:[1,0,0] neg_hi:[1,0,0]
	v_lshlrev_b32_e32 v140, 16, v125
	v_pk_fma_f32 v[146:147], v[144:145], v[146:147], s[34:35] op_sel_hi:[1,1,0]
	v_and_b32_e32 v141, 0xffff0000, v125
	v_pk_fma_f32 v[146:147], v[144:145], v[146:147], s[36:37] op_sel_hi:[1,1,0]
	v_pk_mul_f32 v[138:139], v[138:139], 0.5 op_sel_hi:[1,0]
	v_pk_fma_f32 v[146:147], v[144:145], v[146:147], s[38:39] op_sel_hi:[1,1,0]
	v_lshlrev_b32_e32 v136, 16, v101
	v_pk_fma_f32 v[146:147], v[144:145], v[146:147], s[40:41] op_sel_hi:[1,1,0]
	v_and_b32_e32 v137, 0xffff0000, v101
	v_pk_fma_f32 v[146:147], v[144:145], v[146:147], s[42:43] op_sel_hi:[1,1,0]
	v_pk_mul_f32 v[68:69], v[68:69], v[188:189]
	v_pk_fma_f32 v[144:145], v[144:145], v[146:147], s[44:45] op_sel_hi:[1,1,0]
	v_pk_fma_f32 v[140:141], v[86:87], v[140:141], v[98:99]
	v_pk_mul_f32 v[142:143], v[142:143], v[144:145]
	v_pk_fma_f32 v[136:137], v[90:91], v[136:137], v[140:141]
	v_pk_fma_f32 v[138:139], v[138:139], v[142:143], v[138:139]
	v_mov_b32_dpp v123, v120 row_ror:2 row_mask:0xf bank_mask:0xf bound_ctrl:1
	v_pk_mul_f32 v[68:69], v[68:69], v[138:139]
	v_lshlrev_b32_e32 v138, 16, v115
	v_and_b32_e32 v139, 0xffff0000, v115
	v_pk_fma_f32 v[136:137], v[94:95], v[138:139], v[136:137]
	v_pk_mul_f32 v[70:71], v[70:71], v[188:189]
	v_pk_mul_f32 v[138:139], v[136:137], s[26:27] op_sel_hi:[1,0]
	v_pk_mul_f32 v[136:137], v[136:137], 0.5 op_sel_hi:[1,0]
	v_med3_f32 v138, v138, s71, v224
	v_med3_f32 v139, v139, s71, v224
	v_pk_mul_f32 v[140:141], v[138:139], v[138:139]
	v_mov_b32_dpp v1, v120 row_ror:1 row_mask:0xf bank_mask:0xf bound_ctrl:1
	v_pk_fma_f32 v[142:143], v[140:141], s[28:29], v[118:119] op_sel_hi:[1,0,0] neg_lo:[1,0,0] neg_hi:[1,0,0]
	v_mov_b32_dpp v123, v116 row_shr:2 row_mask:0xf bank_mask:0xf
	v_pk_fma_f32 v[142:143], v[140:141], v[142:143], s[34:35] op_sel_hi:[1,1,0]
	v_mov_b32_dpp v1, v116 row_shr:1 row_mask:0xf bank_mask:0xf
	v_pk_fma_f32 v[142:143], v[140:141], v[142:143], s[36:37] op_sel_hi:[1,1,0]
; __device__ __forceinline__ unsigned cvt_pk_bf16(float lo, float hi) { unsigned r; asm volatile("v_cvt_pk_bf16_f32 %0, %1, %2" : "=v"(r) : "v"(lo), "v"(hi)); return r; }
;     static __device__ __forceinline__ void unpk4(const u32x2 w, float (&o)[4]) { o[0] = bf_lo(w.x); o[1] = bf_hi(w.x); o[2] = bf_lo(w.y); o[3] = bf_hi(w.y); }
;     template <int N> static __device__ __forceinline__ u32x2 dpp_prev(const u32x2 pv, const u32x2 cur) { u32x2 r; r.x = dpp_prev1<N>(pv.x, cur.x); r.y = dpp_prev1<N>(pv.y, cur.y); return r; }
;     static __device__ __forceinline__ u32x2 finish2(const float (&g0)[4], const float (&g1)[4], const float (&g2)[4], const float (&w0)[4], const float (&w1)[4], const float (&w2)[4], const float (&bb)[4],
;                                                     const f32x4 v, float rs) {
;         float h[4];
; #pragma unroll
;         for (int j = 0; j < 4; j += 2) {
;             const f32x2 gc = (f32x2){bb[j] + w0[j] * g2[j] + w1[j] * g1[j] + w2[j] * g0[j], bb[j + 1] + w0[j + 1] * g2[j + 1] + w1[j + 1] * g1[j + 1] + w2[j + 1] * g0[j + 1]};
;             const f32x2 ge = gelu_pk(gc) * ((f32x2){v[j], v[j + 1]} * rs); h[j] = ge.x; h[j + 1] = ge.y; }
;         u32x2 w; w.x = cvt_pk_bf16(h[0], h[1]); w.y = cvt_pk_bf16(h[2], h[3]); return w;
;     __device__ __forceinline__ void operator()(const f32x4 (&acc)[2][2][4][2], const Unit& u, int wr, int wc, int fr, int fq) const {
;     ...
;                 for (int m = 0; m < 4; ++m) { const u32x4 cur = gq[m]; u32x4 hw;
; #pragma unroll
;                     for (int hv = 0; hv < 2; ++hv) { const u32x2 c2 = half2(cur, hv), p2 = half2(pv, hv);
;                         const u32x2 q1 = dpp_prev<1>(p2, c2), q2 = dpp_prev<2>(p2, c2);
;                         float g0[4], g1[4], g2[4]; unpk4(c2, g0); unpk4(q1, g1); unpk4(q2, g2);
;                         const u32x2 r = finish2(g0, g1, g2, w0[hv], w1[hv], w2[hv], bb[hv], acc[ai][bj][m][hv], rs8[ai][m]);
;                         if (hv == 0) { hw.x = r.x; hw.y = r.y; } else { hw.z = r.x; hw.w = r.y; } }
;                     *(u32x4*)(H + (size_t)(R0 + fr + 16 * m) * 2816 + col8) = hw;
	v_cvt_pk_bf16_f32 v68, v68, v69
	v_mov_b32_dpp v125, v121 row_ror:2 row_mask:0xf bank_mask:0xf bound_ctrl:1
	v_pk_fma_f32 v[142:143], v[140:141], v[142:143], s[38:39] op_sel_hi:[1,1,0]
	v_mov_b32_dpp v101, v121 row_ror:1 row_mask:0xf bank_mask:0xf bound_ctrl:1
	v_pk_fma_f32 v[142:143], v[140:141], v[142:143], s[40:41] op_sel_hi:[1,1,0]
	v_mov_b32_dpp v125, v117 row_shr:2 row_mask:0xf bank_mask:0xf
	v_pk_fma_f32 v[142:143], v[140:141], v[142:143], s[42:43] op_sel_hi:[1,1,0]
	v_mov_b32_dpp v101, v117 row_shr:1 row_mask:0xf bank_mask:0xf
	v_pk_fma_f32 v[140:141], v[140:141], v[142:143], s[44:45] op_sel_hi:[1,1,0]
	v_lshlrev_b32_e32 v120, 16, v101
	v_pk_mul_f32 v[138:139], v[138:139], v[140:141]
	v_lshlrev_b32_e32 v140, 16, v116
	v_pk_fma_f32 v[136:137], v[136:137], v[138:139], v[136:137]
	v_and_b32_e32 v141, 0xffff0000, v116
	v_pk_mul_f32 v[70:71], v[70:71], v[136:137]
	v_lshlrev_b32_e32 v136, 16, v123
	v_and_b32_e32 v137, 0xffff0000, v123
	v_cvt_pk_bf16_f32 v69, v70, v71
	v_lshlrev_b32_e32 v70, 16, v1
	v_and_b32_e32 v71, 0xffff0000, v1
	v_pk_fma_f32 v[136:137], v[64:65], v[136:137], v[80:81]
	v_lshlrev_b32_e32 v138, 16, v125
	v_pk_fma_f32 v[70:71], v[72:73], v[70:71], v[136:137]
	v_and_b32_e32 v139, 0xffff0000, v125
	v_pk_fma_f32 v[70:71], v[76:77], v[140:141], v[70:71]
	v_and_b32_e32 v121, 0xffff0000, v101
	v_pk_mul_f32 v[136:137], v[70:71], s[26:27] op_sel_hi:[1,0]
	v_pk_mul_f32 v[70:71], v[70:71], 0.5 op_sel_hi:[1,0]
	v_med3_f32 v136, v136, s71, v224
	v_med3_f32 v137, v137, s71, v224
	v_pk_mul_f32 v[140:141], v[136:137], v[136:137]
	v_pk_mul_f32 v[60:61], v[60:61], v[188:189]
	v_pk_fma_f32 v[142:143], v[140:141], s[28:29], v[118:119] op_sel_hi:[1,0,0] neg_lo:[1,0,0] neg_hi:[1,0,0]
	v_pk_mul_f32 v[62:63], v[62:63], v[188:189]
	v_pk_fma_f32 v[142:143], v[140:141], v[142:143], s[34:35] op_sel_hi:[1,1,0]
	v_mov_b32_dpp v1, v114 row_ror:1 row_mask:0xf bank_mask:0xf bound_ctrl:1
	v_pk_fma_f32 v[142:143], v[140:141], v[142:143], s[36:37] op_sel_hi:[1,1,0]
	v_mov_b32_dpp v101, v115 row_ror:2 row_mask:0xf bank_mask:0xf bound_ctrl:1
	v_pk_fma_f32 v[142:143], v[140:141], v[142:143], s[38:39] op_sel_hi:[1,1,0]
	v_mov_b32_dpp v1, v110 row_shr:1 row_mask:0xf bank_mask:0xf
	v_pk_fma_f32 v[142:143], v[140:141], v[142:143], s[40:41] op_sel_hi:[1,1,0]
	v_mov_b32_dpp v101, v111 row_shr:2 row_mask:0xf bank_mask:0xf
	v_pk_fma_f32 v[142:143], v[140:141], v[142:143], s[42:43] op_sel_hi:[1,1,0]
	v_mov_b32_e32 v187, v186
	v_pk_fma_f32 v[140:141], v[140:141], v[142:143], s[44:45] op_sel_hi:[1,1,0]
	v_pk_mul_f32 v[56:57], v[56:57], v[186:187]
	v_pk_mul_f32 v[136:137], v[136:137], v[140:141]
	v_pk_mul_f32 v[58:59], v[58:59], v[186:187]
	v_pk_fma_f32 v[70:71], v[70:71], v[136:137], v[70:71]
	v_pk_fma_f32 v[136:137], v[66:67], v[138:139], v[82:83]
	v_pk_mul_f32 v[60:61], v[60:61], v[70:71]
	v_lshlrev_b32_e32 v70, 16, v117
	v_and_b32_e32 v71, 0xffff0000, v117
	v_pk_fma_f32 v[120:121], v[74:75], v[120:121], v[136:137]
	v_pk_mul_f32 v[52:53], v[52:53], v[186:187]
	v_pk_fma_f32 v[70:71], v[78:79], v[70:71], v[120:121]
	v_pk_mul_f32 v[54:55], v[54:55], v[186:187]
	v_pk_mul_f32 v[120:121], v[70:71], s[26:27] op_sel_hi:[1,0]
	v_pk_mul_f32 v[70:71], v[70:71], 0.5 op_sel_hi:[1,0]
	v_med3_f32 v120, v120, s71, v224
	v_med3_f32 v121, v121, s71, v224
	v_pk_mul_f32 v[136:137], v[120:121], v[120:121]
	v_mov_b32_e32 v185, v184
	v_pk_fma_f32 v[138:139], v[136:137], s[28:29], v[118:119] op_sel_hi:[1,0,0] neg_lo:[1,0,0] neg_hi:[1,0,0]
	v_pk_mul_f32 v[48:49], v[48:49], v[184:185]
	v_pk_fma_f32 v[138:139], v[136:137], v[138:139], s[34:35] op_sel_hi:[1,1,0]
	v_pk_mul_f32 v[50:51], v[50:51], v[184:185]
	v_pk_fma_f32 v[138:139], v[136:137], v[138:139], s[36:37] op_sel_hi:[1,1,0]
	v_pk_mul_f32 v[44:45], v[44:45], v[184:185]
	v_pk_fma_f32 v[138:139], v[136:137], v[138:139], s[38:39] op_sel_hi:[1,1,0]
	v_pk_mul_f32 v[46:47], v[46:47], v[184:185]
	v_pk_fma_f32 v[138:139], v[136:137], v[138:139], s[40:41] op_sel_hi:[1,1,0]
	v_mov_b32_e32 v3, v2
	v_pk_fma_f32 v[138:139], v[136:137], v[138:139], s[42:43] op_sel_hi:[1,1,0]
	v_pk_mul_f32 v[40:41], v[40:41], v[2:3]
	v_pk_fma_f32 v[136:137], v[136:137], v[138:139], s[44:45] op_sel_hi:[1,1,0]
	v_pk_mul_f32 v[42:43], v[42:43], v[2:3]
	v_pk_mul_f32 v[120:121], v[120:121], v[136:137]
	v_pk_mul_f32 v[36:37], v[36:37], v[2:3]
	v_pk_fma_f32 v[70:71], v[70:71], v[120:121], v[70:71]
	v_lshlrev_b32_e32 v120, 16, v110
	v_pk_mul_f32 v[62:63], v[62:63], v[70:71]
	v_cvt_pk_bf16_f32 v70, v60, v61
	v_lshlrev_b64 v[60:61], 1, v[134:135]
	v_cvt_pk_bf16_f32 v71, v62, v63
	v_lshl_add_u64 v[62:63], v[130:131], 0, v[60:61]
	global_store_dwordx4 v[62:63], v[68:71], off sc1
	v_lshlrev_b32_e32 v62, 16, v1
	v_and_b32_e32 v63, 0xffff0000, v1
	v_mov_b32_dpp v71, v114 row_ror:2 row_mask:0xf bank_mask:0xf bound_ctrl:1
	v_and_b32_e32 v121, 0xffff0000, v110
	v_mov_b32_dpp v69, v115 row_ror:1 row_mask:0xf bank_mask:0xf bound_ctrl:1
	v_mov_b32_dpp v71, v110 row_shr:2 row_mask:0xf bank_mask:0xf
	v_lshlrev_b32_e32 v70, 16, v71
	v_and_b32_e32 v71, 0xffff0000, v71
	v_pk_fma_f32 v[70:71], v[84:85], v[70:71], v[96:97]
	v_mov_b32_dpp v69, v111 row_shr:1 row_mask:0xf bank_mask:0xf
	v_pk_fma_f32 v[62:63], v[88:89], v[62:63], v[70:71]
	v_lshlrev_b32_e32 v114, 16, v101
	v_pk_fma_f32 v[62:63], v[92:93], v[120:121], v[62:63]
	v_and_b32_e32 v115, 0xffff0000, v101
	v_pk_mul_f32 v[70:71], v[62:63], s[26:27] op_sel_hi:[1,0]
	v_pk_mul_f32 v[62:63], v[62:63], 0.5 op_sel_hi:[1,0]
	v_med3_f32 v70, v70, s71, v224
	v_med3_f32 v71, v71, s71, v224
	v_pk_mul_f32 v[120:121], v[70:71], v[70:71]
	v_lshlrev_b32_e32 v68, 16, v69
	v_pk_fma_f32 v[130:131], v[120:121], s[28:29], v[118:119] op_sel_hi:[1,0,0] neg_lo:[1,0,0] neg_hi:[1,0,0]
; __device__ __forceinline__ unsigned cvt_pk_bf16(float lo, float hi) { unsigned r; asm volatile("v_cvt_pk_bf16_f32 %0, %1, %2" : "=v"(r) : "v"(lo), "v"(hi)); return r; }
;     static __device__ __forceinline__ void unpk4(const u32x2 w, float (&o)[4]) { o[0] = bf_lo(w.x); o[1] = bf_hi(w.x); o[2] = bf_lo(w.y); o[3] = bf_hi(w.y); }
;     template <int N> static __device__ __forceinline__ u32x2 dpp_prev(const u32x2 pv, const u32x2 cur) { u32x2 r; r.x = dpp_prev1<N>(pv.x, cur.x); r.y = dpp_prev1<N>(pv.y, cur.y); return r; }
;     static __device__ __forceinline__ u32x2 finish2(const float (&g0)[4], const float (&g1)[4], const float (&g2)[4], const float (&w0)[4], const float (&w1)[4], const float (&w2)[4], const float (&bb)[4],
;                                                     const f32x4 v, float rs) {
;         float h[4];
; #pragma unroll
;         for (int j = 0; j < 4; j += 2) {
;             const f32x2 gc = (f32x2){bb[j] + w0[j] * g2[j] + w1[j] * g1[j] + w2[j] * g0[j], bb[j + 1] + w0[j + 1] * g2[j + 1] + w1[j + 1] * g1[j + 1] + w2[j + 1] * g0[j + 1]};
;             const f32x2 ge = gelu_pk(gc) * ((f32x2){v[j], v[j + 1]} * rs); h[j] = ge.x; h[j + 1] = ge.y; }
;         u32x2 w; w.x = cvt_pk_bf16(h[0], h[1]); w.y = cvt_pk_bf16(h[2], h[3]); return w;
;     __device__ __forceinline__ void operator()(const f32x4 (&acc)[2][2][4][2], const Unit& u, int wr, int wc, int fr, int fq) const {
;     ...
;                 for (int m = 0; m < 4; ++m) { const u32x4 cur = gq[m]; u32x4 hw;
; #pragma unroll
;                     for (int hv = 0; hv < 2; ++hv) { const u32x2 c2 = half2(cur, hv), p2 = half2(pv, hv);
;                         const u32x2 q1 = dpp_prev<1>(p2, c2), q2 = dpp_prev<2>(p2, c2);
;                         float g0[4], g1[4], g2[4]; unpk4(c2, g0); unpk4(q1, g1); unpk4(q2, g2);
;                         const u32x2 r = finish2(g0, g1, g2, w0[hv], w1[hv], w2[hv], bb[hv], acc[ai][bj][m][hv], rs8[ai][m]);
;                         if (hv == 0) { hw.x = r.x; hw.y = r.y; } else { hw.z = r.x; hw.w = r.y; } }
;                     *(u32x4*)(H + (size_t)(R0 + fr + 16 * m) * 2816 + col8) = hw;
	v_and_b32_e32 v69, 0xffff0000, v69
	v_pk_fma_f32 v[130:131], v[120:121], v[130:131], s[34:35] op_sel_hi:[1,1,0]
	v_mov_b32_dpp v1, v116 row_ror:1 row_mask:0xf bank_mask:0xf bound_ctrl:1
	v_pk_fma_f32 v[130:131], v[120:121], v[130:131], s[36:37] op_sel_hi:[1,1,0]
	v_pk_mul_f32 v[2:3], v[38:39], v[2:3]
	v_pk_fma_f32 v[130:131], v[120:121], v[130:131], s[38:39] op_sel_hi:[1,1,0]
	v_mov_b32_dpp v1, v112 row_shr:1 row_mask:0xf bank_mask:0xf
	v_pk_fma_f32 v[130:131], v[120:121], v[130:131], s[40:41] op_sel_hi:[1,1,0]
	v_mov_b32_e32 v101, 0
	v_pk_fma_f32 v[130:131], v[120:121], v[130:131], s[42:43] op_sel_hi:[1,1,0]
	s_nop 0
	v_pk_fma_f32 v[120:121], v[120:121], v[130:131], s[44:45] op_sel_hi:[1,1,0]
	s_nop 0
	v_pk_mul_f32 v[70:71], v[70:71], v[120:121]
	s_nop 0
	v_pk_fma_f32 v[62:63], v[62:63], v[70:71], v[62:63]
	v_pk_fma_f32 v[70:71], v[86:87], v[114:115], v[98:99]
	v_pk_mul_f32 v[56:57], v[56:57], v[62:63]
	v_lshlrev_b32_e32 v62, 16, v111
	v_and_b32_e32 v63, 0xffff0000, v111
	v_pk_fma_f32 v[68:69], v[90:91], v[68:69], v[70:71]
	v_cvt_pk_bf16_f32 v56, v56, v57
	s_nop 0
	v_pk_fma_f32 v[62:63], v[94:95], v[62:63], v[68:69]
	s_nop 0
	v_pk_mul_f32 v[68:69], v[62:63], s[26:27] op_sel_hi:[1,0]
	v_pk_mul_f32 v[62:63], v[62:63], 0.5 op_sel_hi:[1,0]
	v_med3_f32 v68, v68, s71, v224
	v_med3_f32 v69, v69, s71, v224
	v_pk_mul_f32 v[70:71], v[68:69], v[68:69]
	s_nop 0
	v_pk_fma_f32 v[114:115], v[70:71], s[28:29], v[118:119] op_sel_hi:[1,0,0] neg_lo:[1,0,0] neg_hi:[1,0,0]
	s_nop 0
	v_pk_fma_f32 v[114:115], v[70:71], v[114:115], s[34:35] op_sel_hi:[1,1,0]
	s_nop 0
	v_pk_fma_f32 v[114:115], v[70:71], v[114:115], s[36:37] op_sel_hi:[1,1,0]
	s_nop 0
	v_pk_fma_f32 v[114:115], v[70:71], v[114:115], s[38:39] op_sel_hi:[1,1,0]
	s_nop 0
	v_pk_fma_f32 v[114:115], v[70:71], v[114:115], s[40:41] op_sel_hi:[1,1,0]
	s_nop 0
	v_pk_fma_f32 v[114:115], v[70:71], v[114:115], s[42:43] op_sel_hi:[1,1,0]
	s_nop 0
	v_pk_fma_f32 v[70:71], v[70:71], v[114:115], s[44:45] op_sel_hi:[1,1,0]
	v_lshlrev_b32_e32 v114, 16, v112
	v_pk_mul_f32 v[68:69], v[68:69], v[70:71]
	v_and_b32_e32 v115, 0xffff0000, v112
	v_pk_fma_f32 v[62:63], v[62:63], v[68:69], v[62:63]
	v_mov_b32_dpp v69, v116 row_ror:2 row_mask:0xf bank_mask:0xf bound_ctrl:1
	v_pk_mul_f32 v[58:59], v[58:59], v[62:63]
	v_mov_b32_dpp v63, v117 row_ror:1 row_mask:0xf bank_mask:0xf bound_ctrl:1
	v_mov_b32_dpp v69, v112 row_shr:2 row_mask:0xf bank_mask:0xf
	v_lshlrev_b32_e32 v68, 16, v69
	v_and_b32_e32 v69, 0xffff0000, v69
	v_cvt_pk_bf16_f32 v57, v58, v59
	v_lshlrev_b32_e32 v58, 16, v1
	v_and_b32_e32 v59, 0xffff0000, v1
	v_pk_fma_f32 v[68:69], v[64:65], v[68:69], v[80:81]
	v_mov_b32_dpp v71, v117 row_ror:2 row_mask:0xf bank_mask:0xf bound_ctrl:1
	v_pk_fma_f32 v[58:59], v[72:73], v[58:59], v[68:69]
	v_mov_b32_dpp v63, v113 row_shr:1 row_mask:0xf bank_mask:0xf
	v_pk_fma_f32 v[58:59], v[76:77], v[114:115], v[58:59]
	v_mov_b32_dpp v71, v113 row_shr:2 row_mask:0xf bank_mask:0xf
	v_pk_mul_f32 v[68:69], v[58:59], s[26:27] op_sel_hi:[1,0]
	v_lshlrev_b32_e32 v70, 16, v71
	v_med3_f32 v68, v68, s71, v224
	v_med3_f32 v69, v69, s71, v224
	v_pk_mul_f32 v[114:115], v[68:69], v[68:69]
	v_and_b32_e32 v71, 0xffff0000, v71
	v_pk_fma_f32 v[116:117], v[114:115], s[28:29], v[118:119] op_sel_hi:[1,0,0] neg_lo:[1,0,0] neg_hi:[1,0,0]
	v_pk_mul_f32 v[58:59], v[58:59], 0.5 op_sel_hi:[1,0]
	v_pk_fma_f32 v[116:117], v[114:115], v[116:117], s[34:35] op_sel_hi:[1,1,0]
	v_lshlrev_b32_e32 v62, 16, v63
	v_pk_fma_f32 v[116:117], v[114:115], v[116:117], s[36:37] op_sel_hi:[1,1,0]
	v_and_b32_e32 v63, 0xffff0000, v63
	v_pk_fma_f32 v[116:117], v[114:115], v[116:117], s[38:39] op_sel_hi:[1,1,0]
	v_mov_b32_dpp v1, v110 row_ror:1 row_mask:0xf bank_mask:0xf bound_ctrl:1
	v_pk_fma_f32 v[116:117], v[114:115], v[116:117], s[40:41] op_sel_hi:[1,1,0]
	s_nop 0
	v_pk_fma_f32 v[116:117], v[114:115], v[116:117], s[42:43] op_sel_hi:[1,1,0]
	v_mov_b32_dpp v1, v106 row_shr:1 row_mask:0xf bank_mask:0xf
	v_pk_fma_f32 v[114:115], v[114:115], v[116:117], s[44:45] op_sel_hi:[1,1,0]
	s_nop 0
	v_pk_mul_f32 v[68:69], v[68:69], v[114:115]
	s_nop 0
	v_pk_fma_f32 v[58:59], v[58:59], v[68:69], v[58:59]
	v_pk_fma_f32 v[68:69], v[66:67], v[70:71], v[82:83]
	v_pk_mul_f32 v[52:53], v[52:53], v[58:59]
	v_lshlrev_b32_e32 v58, 16, v113
	v_and_b32_e32 v59, 0xffff0000, v113
	v_pk_fma_f32 v[62:63], v[74:75], v[62:63], v[68:69]
	s_nop 0
	v_pk_fma_f32 v[58:59], v[78:79], v[58:59], v[62:63]
	s_nop 0
	v_pk_mul_f32 v[62:63], v[58:59], s[26:27] op_sel_hi:[1,0]
	v_pk_mul_f32 v[58:59], v[58:59], 0.5 op_sel_hi:[1,0]
	v_med3_f32 v62, v62, s71, v224
	v_med3_f32 v63, v63, s71, v224
	v_pk_mul_f32 v[68:69], v[62:63], v[62:63]
	s_nop 0
	v_pk_fma_f32 v[70:71], v[68:69], s[28:29], v[118:119] op_sel_hi:[1,0,0] neg_lo:[1,0,0] neg_hi:[1,0,0]
	s_nop 0
	v_pk_fma_f32 v[70:71], v[68:69], v[70:71], s[34:35] op_sel_hi:[1,1,0]
	s_nop 0
	v_pk_fma_f32 v[70:71], v[68:69], v[70:71], s[36:37] op_sel_hi:[1,1,0]
	s_nop 0
	v_pk_fma_f32 v[70:71], v[68:69], v[70:71], s[38:39] op_sel_hi:[1,1,0]
	s_nop 0
	v_pk_fma_f32 v[70:71], v[68:69], v[70:71], s[40:41] op_sel_hi:[1,1,0]
	s_nop 0
	v_pk_fma_f32 v[70:71], v[68:69], v[70:71], s[42:43] op_sel_hi:[1,1,0]
	s_nop 0
	v_pk_fma_f32 v[68:69], v[68:69], v[70:71], s[44:45] op_sel_hi:[1,1,0]
	s_nop 0
	v_pk_mul_f32 v[62:63], v[62:63], v[68:69]
	s_nop 0
	v_pk_fma_f32 v[58:59], v[58:59], v[62:63], v[58:59]
	v_lshlrev_b32_e32 v62, 16, v106
	v_pk_mul_f32 v[54:55], v[54:55], v[58:59]
	v_cvt_pk_bf16_f32 v58, v52, v53
	v_lshl_add_u64 v[52:53], v[176:177], 0, v[60:61]
	v_cvt_pk_bf16_f32 v59, v54, v55
	global_store_dwordx4 v[52:53], v[56:59], off sc1
	v_lshlrev_b32_e32 v52, 16, v1
	v_and_b32_e32 v53, 0xffff0000, v1
; __device__ __forceinline__ unsigned cvt_pk_bf16(float lo, float hi) { unsigned r; asm volatile("v_cvt_pk_bf16_f32 %0, %1, %2" : "=v"(r) : "v"(lo), "v"(hi)); return r; }
;     static __device__ __forceinline__ void unpk4(const u32x2 w, float (&o)[4]) { o[0] = bf_lo(w.x); o[1] = bf_hi(w.x); o[2] = bf_lo(w.y); o[3] = bf_hi(w.y); }
;     template <int N> static __device__ __forceinline__ u32x2 dpp_prev(const u32x2 pv, const u32x2 cur) { u32x2 r; r.x = dpp_prev1<N>(pv.x, cur.x); r.y = dpp_prev1<N>(pv.y, cur.y); return r; }
;     static __device__ __forceinline__ u32x2 finish2(const float (&g0)[4], const float (&g1)[4], const float (&g2)[4], const float (&w0)[4], const float (&w1)[4], const float (&w2)[4], const float (&bb)[4],
;                                                     const f32x4 v, float rs) {
;         float h[4];
; #pragma unroll
;         for (int j = 0; j < 4; j += 2) {
;             const f32x2 gc = (f32x2){bb[j] + w0[j] * g2[j] + w1[j] * g1[j] + w2[j] * g0[j], bb[j + 1] + w0[j + 1] * g2[j + 1] + w1[j + 1] * g1[j + 1] + w2[j + 1] * g0[j + 1]};
;             const f32x2 ge = gelu_pk(gc) * ((f32x2){v[j], v[j + 1]} * rs); h[j] = ge.x; h[j + 1] = ge.y; }
;         u32x2 w; w.x = cvt_pk_bf16(h[0], h[1]); w.y = cvt_pk_bf16(h[2], h[3]); return w;
;     __device__ __forceinline__ void operator()(const f32x4 (&acc)[2][2][4][2], const Unit& u, int wr, int wc, int fr, int fq) const {
;     ...
;                 for (int m = 0; m < 4; ++m) { const u32x4 cur = gq[m]; u32x4 hw;
; #pragma unroll
;                     for (int hv = 0; hv < 2; ++hv) { const u32x2 c2 = half2(cur, hv), p2 = half2(pv, hv);
;                         const u32x2 q1 = dpp_prev<1>(p2, c2), q2 = dpp_prev<2>(p2, c2);
;                         float g0[4], g1[4], g2[4]; unpk4(c2, g0); unpk4(q1, g1); unpk4(q2, g2);
;                         const u32x2 r = finish2(g0, g1, g2, w0[hv], w1[hv], w2[hv], bb[hv], acc[ai][bj][m][hv], rs8[ai][m]);
;                         if (hv == 0) { hw.x = r.x; hw.y = r.y; } else { hw.z = r.x; hw.w = r.y; } }
;                     *(u32x4*)(H + (size_t)(R0 + fr + 16 * m) * 2816 + col8) = hw;
	v_mov_b32_dpp v57, v110 row_ror:2 row_mask:0xf bank_mask:0xf bound_ctrl:1
	v_and_b32_e32 v63, 0xffff0000, v106
	v_mov_b32_dpp v59, v111 row_ror:2 row_mask:0xf bank_mask:0xf bound_ctrl:1
	v_mov_b32_dpp v57, v106 row_shr:2 row_mask:0xf bank_mask:0xf
	v_lshlrev_b32_e32 v56, 16, v57
	v_and_b32_e32 v57, 0xffff0000, v57
	v_pk_fma_f32 v[56:57], v[84:85], v[56:57], v[96:97]
	v_mov_b32_dpp v55, v111 row_ror:1 row_mask:0xf bank_mask:0xf bound_ctrl:1
	v_pk_fma_f32 v[52:53], v[88:89], v[52:53], v[56:57]
	v_mov_b32_dpp v59, v107 row_shr:2 row_mask:0xf bank_mask:0xf
	v_pk_fma_f32 v[52:53], v[92:93], v[62:63], v[52:53]
	v_mov_b32_dpp v55, v107 row_shr:1 row_mask:0xf bank_mask:0xf
	v_pk_mul_f32 v[56:57], v[52:53], s[26:27] op_sel_hi:[1,0]
	v_lshlrev_b32_e32 v58, 16, v59
	v_med3_f32 v56, v56, s71, v224
	v_med3_f32 v57, v57, s71, v224
	v_pk_mul_f32 v[62:63], v[56:57], v[56:57]
	v_and_b32_e32 v59, 0xffff0000, v59
	v_pk_fma_f32 v[68:69], v[62:63], s[28:29], v[118:119] op_sel_hi:[1,0,0] neg_lo:[1,0,0] neg_hi:[1,0,0]
	v_pk_mul_f32 v[52:53], v[52:53], 0.5 op_sel_hi:[1,0]
	v_pk_fma_f32 v[68:69], v[62:63], v[68:69], s[34:35] op_sel_hi:[1,1,0]
	v_lshlrev_b32_e32 v54, 16, v55
	v_pk_fma_f32 v[68:69], v[62:63], v[68:69], s[36:37] op_sel_hi:[1,1,0]
	v_and_b32_e32 v55, 0xffff0000, v55
	v_pk_fma_f32 v[68:69], v[62:63], v[68:69], s[38:39] op_sel_hi:[1,1,0]
	v_mov_b32_dpp v1, v112 row_ror:1 row_mask:0xf bank_mask:0xf bound_ctrl:1
	v_pk_fma_f32 v[68:69], v[62:63], v[68:69], s[40:41] op_sel_hi:[1,1,0]
	s_nop 0
	v_pk_fma_f32 v[68:69], v[62:63], v[68:69], s[42:43] op_sel_hi:[1,1,0]
	v_mov_b32_dpp v1, v108 row_shr:1 row_mask:0xf bank_mask:0xf
	v_pk_fma_f32 v[62:63], v[62:63], v[68:69], s[44:45] op_sel_hi:[1,1,0]
	s_nop 0
	v_pk_mul_f32 v[56:57], v[56:57], v[62:63]
	s_nop 0
	v_pk_fma_f32 v[52:53], v[52:53], v[56:57], v[52:53]
	v_pk_fma_f32 v[56:57], v[86:87], v[58:59], v[98:99]
	v_pk_mul_f32 v[48:49], v[48:49], v[52:53]
	v_lshlrev_b32_e32 v52, 16, v107
	v_and_b32_e32 v53, 0xffff0000, v107
	v_pk_fma_f32 v[54:55], v[90:91], v[54:55], v[56:57]
	v_cvt_pk_bf16_f32 v48, v48, v49
	s_nop 0
	v_pk_fma_f32 v[52:53], v[94:95], v[52:53], v[54:55]
	s_nop 0
	v_pk_mul_f32 v[54:55], v[52:53], s[26:27] op_sel_hi:[1,0]
	v_pk_mul_f32 v[52:53], v[52:53], 0.5 op_sel_hi:[1,0]
	v_med3_f32 v54, v54, s71, v224
	v_med3_f32 v55, v55, s71, v224
	v_pk_mul_f32 v[56:57], v[54:55], v[54:55]
	s_nop 0
	v_pk_fma_f32 v[58:59], v[56:57], s[28:29], v[118:119] op_sel_hi:[1,0,0] neg_lo:[1,0,0] neg_hi:[1,0,0]
	s_nop 0
	v_pk_fma_f32 v[58:59], v[56:57], v[58:59], s[34:35] op_sel_hi:[1,1,0]
	s_nop 0
	v_pk_fma_f32 v[58:59], v[56:57], v[58:59], s[36:37] op_sel_hi:[1,1,0]
	s_nop 0
	v_pk_fma_f32 v[58:59], v[56:57], v[58:59], s[38:39] op_sel_hi:[1,1,0]
	s_nop 0
	v_pk_fma_f32 v[58:59], v[56:57], v[58:59], s[40:41] op_sel_hi:[1,1,0]
	s_nop 0
	v_pk_fma_f32 v[58:59], v[56:57], v[58:59], s[42:43] op_sel_hi:[1,1,0]
	s_nop 0
	v_pk_fma_f32 v[56:57], v[56:57], v[58:59], s[44:45] op_sel_hi:[1,1,0]
	v_lshlrev_b32_e32 v58, 16, v108
	v_pk_mul_f32 v[54:55], v[54:55], v[56:57]
	v_and_b32_e32 v59, 0xffff0000, v108
	v_pk_fma_f32 v[52:53], v[52:53], v[54:55], v[52:53]
	v_mov_b32_dpp v55, v112 row_ror:2 row_mask:0xf bank_mask:0xf bound_ctrl:1
	v_pk_mul_f32 v[50:51], v[50:51], v[52:53]
	v_mov_b32_dpp v57, v113 row_ror:2 row_mask:0xf bank_mask:0xf bound_ctrl:1
	v_mov_b32_dpp v55, v108 row_shr:2 row_mask:0xf bank_mask:0xf
	v_lshlrev_b32_e32 v54, 16, v55
	v_and_b32_e32 v55, 0xffff0000, v55
	v_cvt_pk_bf16_f32 v49, v50, v51
	v_lshlrev_b32_e32 v50, 16, v1
	v_and_b32_e32 v51, 0xffff0000, v1
	v_pk_fma_f32 v[54:55], v[64:65], v[54:55], v[80:81]
	v_mov_b32_dpp v53, v113 row_ror:1 row_mask:0xf bank_mask:0xf bound_ctrl:1
	v_pk_fma_f32 v[50:51], v[72:73], v[50:51], v[54:55]
	v_mov_b32_dpp v57, v109 row_shr:2 row_mask:0xf bank_mask:0xf
	v_pk_fma_f32 v[50:51], v[76:77], v[58:59], v[50:51]
	v_mov_b32_dpp v53, v109 row_shr:1 row_mask:0xf bank_mask:0xf
	v_pk_mul_f32 v[54:55], v[50:51], s[26:27] op_sel_hi:[1,0]
	v_lshlrev_b32_e32 v56, 16, v57
	v_med3_f32 v54, v54, s71, v224
	v_med3_f32 v55, v55, s71, v224
	v_pk_mul_f32 v[58:59], v[54:55], v[54:55]
	v_and_b32_e32 v57, 0xffff0000, v57
	v_pk_fma_f32 v[62:63], v[58:59], s[28:29], v[118:119] op_sel_hi:[1,0,0] neg_lo:[1,0,0] neg_hi:[1,0,0]
	v_pk_mul_f32 v[50:51], v[50:51], 0.5 op_sel_hi:[1,0]
	v_pk_fma_f32 v[62:63], v[58:59], v[62:63], s[34:35] op_sel_hi:[1,1,0]
	v_lshlrev_b32_e32 v52, 16, v53
	v_pk_fma_f32 v[62:63], v[58:59], v[62:63], s[36:37] op_sel_hi:[1,1,0]
	v_and_b32_e32 v53, 0xffff0000, v53
	v_pk_fma_f32 v[62:63], v[58:59], v[62:63], s[38:39] op_sel_hi:[1,1,0]
	v_mov_b32_dpp v1, v106 row_ror:1 row_mask:0xf bank_mask:0xf bound_ctrl:1
	v_pk_fma_f32 v[62:63], v[58:59], v[62:63], s[40:41] op_sel_hi:[1,1,0]
	s_nop 0
	v_pk_fma_f32 v[62:63], v[58:59], v[62:63], s[42:43] op_sel_hi:[1,1,0]
	v_mov_b32_dpp v1, v102 row_shr:1 row_mask:0xf bank_mask:0xf
	v_pk_fma_f32 v[58:59], v[58:59], v[62:63], s[44:45] op_sel_hi:[1,1,0]
	s_nop 0
	v_pk_mul_f32 v[54:55], v[54:55], v[58:59]
	s_nop 0
	v_pk_fma_f32 v[50:51], v[50:51], v[54:55], v[50:51]
	v_pk_fma_f32 v[54:55], v[66:67], v[56:57], v[82:83]
	v_pk_mul_f32 v[44:45], v[44:45], v[50:51]
	v_lshlrev_b32_e32 v50, 16, v109
	v_and_b32_e32 v51, 0xffff0000, v109
	v_pk_fma_f32 v[52:53], v[74:75], v[52:53], v[54:55]
	s_nop 0
	v_pk_fma_f32 v[50:51], v[78:79], v[50:51], v[52:53]
	s_nop 0
	v_pk_mul_f32 v[52:53], v[50:51], s[26:27] op_sel_hi:[1,0]
	v_pk_mul_f32 v[50:51], v[50:51], 0.5 op_sel_hi:[1,0]
	v_med3_f32 v52, v52, s71, v224
	v_med3_f32 v53, v53, s71, v224
	v_pk_mul_f32 v[54:55], v[52:53], v[52:53]
	s_nop 0
	v_pk_fma_f32 v[56:57], v[54:55], s[28:29], v[118:119] op_sel_hi:[1,0,0] neg_lo:[1,0,0] neg_hi:[1,0,0]
; __device__ __forceinline__ unsigned cvt_pk_bf16(float lo, float hi) { unsigned r; asm volatile("v_cvt_pk_bf16_f32 %0, %1, %2" : "=v"(r) : "v"(lo), "v"(hi)); return r; }
;     static __device__ __forceinline__ void unpk4(const u32x2 w, float (&o)[4]) { o[0] = bf_lo(w.x); o[1] = bf_hi(w.x); o[2] = bf_lo(w.y); o[3] = bf_hi(w.y); }
;     template <int N> static __device__ __forceinline__ u32x2 dpp_prev(const u32x2 pv, const u32x2 cur) { u32x2 r; r.x = dpp_prev1<N>(pv.x, cur.x); r.y = dpp_prev1<N>(pv.y, cur.y); return r; }
;     static __device__ __forceinline__ u32x2 finish2(const float (&g0)[4], const float (&g1)[4], const float (&g2)[4], const float (&w0)[4], const float (&w1)[4], const float (&w2)[4], const float (&bb)[4],
;                                                     const f32x4 v, float rs) {
;         float h[4];
; #pragma unroll
;         for (int j = 0; j < 4; j += 2) {
;             const f32x2 gc = (f32x2){bb[j] + w0[j] * g2[j] + w1[j] * g1[j] + w2[j] * g0[j], bb[j + 1] + w0[j + 1] * g2[j + 1] + w1[j + 1] * g1[j + 1] + w2[j + 1] * g0[j + 1]};
;             const f32x2 ge = gelu_pk(gc) * ((f32x2){v[j], v[j + 1]} * rs); h[j] = ge.x; h[j + 1] = ge.y; }
;         u32x2 w; w.x = cvt_pk_bf16(h[0], h[1]); w.y = cvt_pk_bf16(h[2], h[3]); return w;
;     __device__ __forceinline__ void operator()(const f32x4 (&acc)[2][2][4][2], const Unit& u, int wr, int wc, int fr, int fq) const {
;     ...
;                 for (int m = 0; m < 4; ++m) { const u32x4 cur = gq[m]; u32x4 hw;
; #pragma unroll
;                     for (int hv = 0; hv < 2; ++hv) { const u32x2 c2 = half2(cur, hv), p2 = half2(pv, hv);
;                         const u32x2 q1 = dpp_prev<1>(p2, c2), q2 = dpp_prev<2>(p2, c2);
;                         float g0[4], g1[4], g2[4]; unpk4(c2, g0); unpk4(q1, g1); unpk4(q2, g2);
;                         const u32x2 r = finish2(g0, g1, g2, w0[hv], w1[hv], w2[hv], bb[hv], acc[ai][bj][m][hv], rs8[ai][m]);
;                         if (hv == 0) { hw.x = r.x; hw.y = r.y; } else { hw.z = r.x; hw.w = r.y; } }
;                     *(u32x4*)(H + (size_t)(R0 + fr + 16 * m) * 2816 + col8) = hw;
	s_nop 0
	v_pk_fma_f32 v[56:57], v[54:55], v[56:57], s[34:35] op_sel_hi:[1,1,0]
	s_nop 0
	v_pk_fma_f32 v[56:57], v[54:55], v[56:57], s[36:37] op_sel_hi:[1,1,0]
	s_nop 0
	v_pk_fma_f32 v[56:57], v[54:55], v[56:57], s[38:39] op_sel_hi:[1,1,0]
	s_nop 0
	v_pk_fma_f32 v[56:57], v[54:55], v[56:57], s[40:41] op_sel_hi:[1,1,0]
	s_nop 0
	v_pk_fma_f32 v[56:57], v[54:55], v[56:57], s[42:43] op_sel_hi:[1,1,0]
	s_nop 0
	v_pk_fma_f32 v[54:55], v[54:55], v[56:57], s[44:45] op_sel_hi:[1,1,0]
	v_lshl_add_u64 v[56:57], v[166:167], 0, v[60:61]
	v_pk_mul_f32 v[52:53], v[52:53], v[54:55]
	s_nop 0
	v_pk_fma_f32 v[50:51], v[50:51], v[52:53], v[50:51]
	v_lshlrev_b32_e32 v52, 16, v102
	v_pk_mul_f32 v[46:47], v[46:47], v[50:51]
	v_cvt_pk_bf16_f32 v50, v44, v45
	v_lshl_add_u64 v[44:45], v[172:173], 0, v[60:61]
	v_cvt_pk_bf16_f32 v51, v46, v47
	global_store_dwordx4 v[44:45], v[48:51], off sc1
	v_lshlrev_b32_e32 v44, 16, v1
	v_and_b32_e32 v45, 0xffff0000, v1
	v_mov_b32_dpp v49, v106 row_ror:2 row_mask:0xf bank_mask:0xf bound_ctrl:1
	v_and_b32_e32 v53, 0xffff0000, v102
	v_mov_b32_dpp v51, v107 row_ror:2 row_mask:0xf bank_mask:0xf bound_ctrl:1
	v_mov_b32_dpp v49, v102 row_shr:2 row_mask:0xf bank_mask:0xf
	v_lshlrev_b32_e32 v48, 16, v49
	v_and_b32_e32 v49, 0xffff0000, v49
	v_pk_fma_f32 v[48:49], v[84:85], v[48:49], v[96:97]
	v_mov_b32_dpp v47, v107 row_ror:1 row_mask:0xf bank_mask:0xf bound_ctrl:1
	v_pk_fma_f32 v[44:45], v[88:89], v[44:45], v[48:49]
	v_mov_b32_dpp v51, v103 row_shr:2 row_mask:0xf bank_mask:0xf
	v_pk_fma_f32 v[44:45], v[92:93], v[52:53], v[44:45]
	v_mov_b32_dpp v47, v103 row_shr:1 row_mask:0xf bank_mask:0xf
	v_pk_mul_f32 v[48:49], v[44:45], s[26:27] op_sel_hi:[1,0]
	v_lshlrev_b32_e32 v50, 16, v51
	v_med3_f32 v48, v48, s71, v224
	v_med3_f32 v49, v49, s71, v224
	v_pk_mul_f32 v[52:53], v[48:49], v[48:49]
	v_and_b32_e32 v51, 0xffff0000, v51
	v_pk_fma_f32 v[54:55], v[52:53], s[28:29], v[118:119] op_sel_hi:[1,0,0] neg_lo:[1,0,0] neg_hi:[1,0,0]
	v_pk_mul_f32 v[44:45], v[44:45], 0.5 op_sel_hi:[1,0]
	v_pk_fma_f32 v[54:55], v[52:53], v[54:55], s[34:35] op_sel_hi:[1,1,0]
	v_lshlrev_b32_e32 v46, 16, v47
	v_pk_fma_f32 v[54:55], v[52:53], v[54:55], s[36:37] op_sel_hi:[1,1,0]
	v_and_b32_e32 v47, 0xffff0000, v47
	v_pk_fma_f32 v[54:55], v[52:53], v[54:55], s[38:39] op_sel_hi:[1,1,0]
	v_mov_b32_dpp v1, v108 row_ror:1 row_mask:0xf bank_mask:0xf bound_ctrl:1
	v_pk_fma_f32 v[54:55], v[52:53], v[54:55], s[40:41] op_sel_hi:[1,1,0]
	v_mov_b32_e32 v102, 0
	v_pk_fma_f32 v[54:55], v[52:53], v[54:55], s[42:43] op_sel_hi:[1,1,0]
	v_mov_b32_dpp v1, v104 row_shr:1 row_mask:0xf bank_mask:0xf
	v_pk_fma_f32 v[52:53], v[52:53], v[54:55], s[44:45] op_sel_hi:[1,1,0]
	s_nop 0
	v_pk_mul_f32 v[48:49], v[48:49], v[52:53]
	s_nop 0
	v_pk_fma_f32 v[44:45], v[44:45], v[48:49], v[44:45]
	v_pk_fma_f32 v[48:49], v[86:87], v[50:51], v[98:99]
	v_pk_mul_f32 v[40:41], v[40:41], v[44:45]
	v_lshlrev_b32_e32 v44, 16, v103
	v_and_b32_e32 v45, 0xffff0000, v103
	v_pk_fma_f32 v[46:47], v[90:91], v[46:47], v[48:49]
	v_cvt_pk_bf16_f32 v52, v40, v41
	v_lshlrev_b32_e32 v40, 16, v1
	v_pk_fma_f32 v[44:45], v[94:95], v[44:45], v[46:47]
	v_and_b32_e32 v41, 0xffff0000, v1
	v_pk_mul_f32 v[46:47], v[44:45], s[26:27] op_sel_hi:[1,0]
	v_pk_mul_f32 v[44:45], v[44:45], 0.5 op_sel_hi:[1,0]
	v_med3_f32 v46, v46, s71, v224
	v_med3_f32 v47, v47, s71, v224
	v_pk_mul_f32 v[48:49], v[46:47], v[46:47]
	v_mov_b32_e32 v103, 0
	v_pk_fma_f32 v[50:51], v[48:49], s[28:29], v[118:119] op_sel_hi:[1,0,0] neg_lo:[1,0,0] neg_hi:[1,0,0]
	s_nop 0
	v_pk_fma_f32 v[50:51], v[48:49], v[50:51], s[34:35] op_sel_hi:[1,1,0]
	s_nop 0
	v_pk_fma_f32 v[50:51], v[48:49], v[50:51], s[36:37] op_sel_hi:[1,1,0]
	s_nop 0
	v_pk_fma_f32 v[50:51], v[48:49], v[50:51], s[38:39] op_sel_hi:[1,1,0]
	s_nop 0
	v_pk_fma_f32 v[50:51], v[48:49], v[50:51], s[40:41] op_sel_hi:[1,1,0]
	s_nop 0
	v_pk_fma_f32 v[50:51], v[48:49], v[50:51], s[42:43] op_sel_hi:[1,1,0]
	s_nop 0
	v_pk_fma_f32 v[48:49], v[48:49], v[50:51], s[44:45] op_sel_hi:[1,1,0]
	s_nop 0
	v_pk_mul_f32 v[46:47], v[46:47], v[48:49]
	v_lshlrev_b32_e32 v48, 16, v104
	v_pk_fma_f32 v[44:45], v[44:45], v[46:47], v[44:45]
	v_and_b32_e32 v49, 0xffff0000, v104
	v_pk_mul_f32 v[42:43], v[42:43], v[44:45]
	v_mov_b32_dpp v45, v108 row_ror:2 row_mask:0xf bank_mask:0xf bound_ctrl:1
	v_mov_b32_dpp v47, v109 row_ror:2 row_mask:0xf bank_mask:0xf bound_ctrl:1
	v_cvt_pk_bf16_f32 v53, v42, v43
	v_mov_b32_dpp v43, v109 row_ror:1 row_mask:0xf bank_mask:0xf bound_ctrl:1
	v_mov_b32_dpp v45, v104 row_shr:2 row_mask:0xf bank_mask:0xf
	v_lshlrev_b32_e32 v44, 16, v45
	v_and_b32_e32 v45, 0xffff0000, v45
	v_pk_fma_f32 v[44:45], v[64:65], v[44:45], v[80:81]
	v_mov_b32_dpp v47, v105 row_shr:2 row_mask:0xf bank_mask:0xf
	v_pk_fma_f32 v[40:41], v[72:73], v[40:41], v[44:45]
	v_mov_b32_dpp v43, v105 row_shr:1 row_mask:0xf bank_mask:0xf
	v_pk_fma_f32 v[40:41], v[76:77], v[48:49], v[40:41]
	v_lshlrev_b32_e32 v46, 16, v47
	v_pk_mul_f32 v[44:45], v[40:41], s[26:27] op_sel_hi:[1,0]
	v_and_b32_e32 v47, 0xffff0000, v47
	v_med3_f32 v44, v44, s71, v224
	v_med3_f32 v45, v45, s71, v224
	v_pk_mul_f32 v[48:49], v[44:45], v[44:45]
	v_pk_mul_f32 v[40:41], v[40:41], 0.5 op_sel_hi:[1,0]
	v_pk_fma_f32 v[50:51], v[48:49], s[28:29], v[118:119] op_sel_hi:[1,0,0] neg_lo:[1,0,0] neg_hi:[1,0,0]
	v_lshlrev_b32_e32 v42, 16, v43
	v_pk_fma_f32 v[50:51], v[48:49], v[50:51], s[34:35] op_sel_hi:[1,1,0]
	v_and_b32_e32 v43, 0xffff0000, v43
	v_pk_fma_f32 v[50:51], v[48:49], v[50:51], s[36:37] op_sel_hi:[1,1,0]
	s_nop 0
	v_pk_fma_f32 v[50:51], v[48:49], v[50:51], s[38:39] op_sel_hi:[1,1,0]
	s_nop 0
	v_pk_fma_f32 v[50:51], v[48:49], v[50:51], s[40:41] op_sel_hi:[1,1,0]
	s_nop 0
;     static __device__ __forceinline__ void unpk4(const u32x2 w, float (&o)[4]) { o[0] = bf_lo(w.x); o[1] = bf_hi(w.x); o[2] = bf_lo(w.y); o[3] = bf_hi(w.y); }
;     template <int N> static __device__ __forceinline__ u32x2 dpp_prev(const u32x2 pv, const u32x2 cur) { u32x2 r; r.x = dpp_prev1<N>(pv.x, cur.x); r.y = dpp_prev1<N>(pv.y, cur.y); return r; }
;     __device__ __forceinline__ void operator()(const f32x4 (&acc)[2][2][4][2], const Unit& u, int wr, int wc, int fr, int fq) const {
;     ...
;             for (int ai = 0; ai < 2; ++ai) { const int R0 = u.rb + ai * HALF + wr * 64; const bf16_t* gp = G + (size_t)(R0 + fr) * 2816 + col8;
;                 u32x4 gq[4], prv = (u32x4){0u, 0u, 0u, 0u};
; #pragma unroll
;                 for (int m = 0; m < 4; ++m) gq[m] = *(const u32x4*)(gp + (size_t)m * 16 * 2816);
;                 if ((R0 & 8191) != 0) prv = *(const u32x4*)(gp - (size_t)16 * 2816);
;                 u32x4 pv = prv;
; #pragma unroll
;                 for (int m = 0; m < 4; ++m) { const u32x4 cur = gq[m]; u32x4 hw;
; #pragma unroll
;                     for (int hv = 0; hv < 2; ++hv) { const u32x2 c2 = half2(cur, hv), p2 = half2(pv, hv);
;                         const u32x2 q1 = dpp_prev<1>(p2, c2), q2 = dpp_prev<2>(p2, c2);
;                         float g0[4], g1[4], g2[4]; unpk4(c2, g0); unpk4(q1, g1); unpk4(q2, g2);
;                         const u32x2 r = finish2(g0, g1, g2, w0[hv], w1[hv], w2[hv], bb[hv], acc[ai][bj][m][hv], rs8[ai][m]);
;                         if (hv == 0) { hw.x = r.x; hw.y = r.y; } else { hw.z = r.x; hw.w = r.y; } }
;                     *(u32x4*)(H + (size_t)(R0 + fr + 16 * m) * 2816 + col8) = hw;
	v_pk_fma_f32 v[50:51], v[48:49], v[50:51], s[42:43] op_sel_hi:[1,1,0]
	s_nop 0
	v_pk_fma_f32 v[48:49], v[48:49], v[50:51], s[44:45] op_sel_hi:[1,1,0]
	s_nop 0
	v_pk_mul_f32 v[44:45], v[44:45], v[48:49]
	s_nop 0
	v_pk_fma_f32 v[40:41], v[40:41], v[44:45], v[40:41]
	v_pk_fma_f32 v[44:45], v[66:67], v[46:47], v[82:83]
	v_pk_mul_f32 v[36:37], v[36:37], v[40:41]
	v_lshlrev_b32_e32 v40, 16, v105
	v_and_b32_e32 v41, 0xffff0000, v105
	v_pk_fma_f32 v[42:43], v[74:75], v[42:43], v[44:45]
	v_cvt_pk_bf16_f32 v54, v36, v37
	s_nop 0
	v_pk_fma_f32 v[40:41], v[78:79], v[40:41], v[42:43]
	s_nop 0
	v_pk_mul_f32 v[42:43], v[40:41], s[26:27] op_sel_hi:[1,0]
	v_pk_mul_f32 v[40:41], v[40:41], 0.5 op_sel_hi:[1,0]
	v_med3_f32 v42, v42, s71, v224
	v_med3_f32 v43, v43, s71, v224
	v_pk_mul_f32 v[44:45], v[42:43], v[42:43]
	s_nop 0
	v_pk_fma_f32 v[46:47], v[44:45], s[28:29], v[118:119] op_sel_hi:[1,0,0] neg_lo:[1,0,0] neg_hi:[1,0,0]
	s_nop 0
	v_pk_fma_f32 v[46:47], v[44:45], v[46:47], s[34:35] op_sel_hi:[1,1,0]
	s_nop 0
	v_pk_fma_f32 v[46:47], v[44:45], v[46:47], s[36:37] op_sel_hi:[1,1,0]
	s_nop 0
	v_pk_fma_f32 v[46:47], v[44:45], v[46:47], s[38:39] op_sel_hi:[1,1,0]
	s_nop 0
	v_pk_fma_f32 v[46:47], v[44:45], v[46:47], s[40:41] op_sel_hi:[1,1,0]
	s_nop 0
	v_pk_fma_f32 v[46:47], v[44:45], v[46:47], s[42:43] op_sel_hi:[1,1,0]
	s_nop 0
	v_pk_fma_f32 v[44:45], v[44:45], v[46:47], s[44:45] op_sel_hi:[1,1,0]
	s_nop 0
	v_pk_mul_f32 v[42:43], v[42:43], v[44:45]
	s_nop 0
	v_pk_fma_f32 v[40:41], v[40:41], v[42:43], v[40:41]
	s_nop 0
	v_pk_mul_f32 v[2:3], v[2:3], v[40:41]
	s_nop 0
	v_cvt_pk_bf16_f32 v55, v2, v3
	v_lshl_add_u64 v[2:3], v[164:165], 0, v[60:61]
	v_add_co_u32_e32 v36, vcc, s45, v2
	s_nop 1
	v_addc_co_u32_e32 v37, vcc, 0, v3, vcc
	global_load_dwordx4 v[48:51], v[2:3], off
	global_load_dwordx4 v[44:47], v[36:37], off
	v_add_co_u32_e32 v36, vcc, 0x2c000, v2
	s_nop 1
	v_addc_co_u32_e32 v37, vcc, 0, v3, vcc
	v_add_co_u32_e32 v38, vcc, 0x42000, v2
	s_nop 1
	v_addc_co_u32_e32 v39, vcc, 0, v3, vcc
	global_load_dwordx4 v[40:43], v[36:37], off
	s_nop 0
	global_load_dwordx4 v[36:39], v[38:39], off
	s_andn2_b64 vcc, exec, s[8:9]
	global_store_dwordx4 v[56:57], v[52:55], off sc1
	s_cbranch_vccnz .LBB0_3152
	v_add_co_u32_e32 v2, vcc, 0xfffea000, v2
	s_nop 1
	v_addc_co_u32_e32 v3, vcc, -1, v3, vcc
	global_load_dwordx4 v[100:103], v[2:3], off
.LBB0_3152:
	s_waitcnt vmcnt(0)
	s_nop 0
	v_mov_b32_dpp v55, v100 row_ror:2 row_mask:0xf bank_mask:0xf bound_ctrl:1
	v_mov_b32_dpp v1, v100 row_ror:1 row_mask:0xf bank_mask:0xf bound_ctrl:1
	v_lshlrev_b32_e32 v58, 16, v48
	v_mov_b32_dpp v55, v48 row_shr:2 row_mask:0xf bank_mask:0xf
	v_mov_b32_dpp v1, v48 row_shr:1 row_mask:0xf bank_mask:0xf
	v_lshlrev_b32_e32 v54, 16, v55
	v_and_b32_e32 v55, 0xffff0000, v55
	v_lshlrev_b32_e32 v2, 16, v1
	v_and_b32_e32 v3, 0xffff0000, v1
	v_pk_fma_f32 v[54:55], v[84:85], v[54:55], v[96:97]
	v_and_b32_e32 v59, 0xffff0000, v48
	v_pk_fma_f32 v[2:3], v[88:89], v[2:3], v[54:55]
	v_mov_b32_dpp v57, v101 row_ror:2 row_mask:0xf bank_mask:0xf bound_ctrl:1
	v_pk_fma_f32 v[54:55], v[92:93], v[58:59], v[2:3]
	v_mov_b32_dpp v53, v101 row_ror:1 row_mask:0xf bank_mask:0xf bound_ctrl:1
	v_pk_mul_f32 v[2:3], v[54:55], s[26:27] op_sel_hi:[1,0]
	v_mov_b32_dpp v57, v49 row_shr:2 row_mask:0xf bank_mask:0xf
	v_med3_f32 v58, v2, s71, v224
	v_med3_f32 v59, v3, s71, v224
	v_pk_mul_f32 v[62:63], v[58:59], v[58:59]
	v_mov_b64_e32 v[2:3], s[30:31]
	v_pk_fma_f32 v[68:69], v[62:63], s[28:29], v[2:3] op_sel_hi:[1,0,0] neg_lo:[1,0,0] neg_hi:[1,0,0]
	v_mov_b32_e32 v129, v128
	v_pk_fma_f32 v[68:69], v[62:63], v[68:69], s[34:35] op_sel_hi:[1,1,0]
	v_mov_b32_dpp v53, v49 row_shr:1 row_mask:0xf bank_mask:0xf
	v_pk_fma_f32 v[68:69], v[62:63], v[68:69], s[36:37] op_sel_hi:[1,1,0]
	v_lshlrev_b32_e32 v56, 16, v57
	v_pk_fma_f32 v[68:69], v[62:63], v[68:69], s[38:39] op_sel_hi:[1,1,0]
	v_and_b32_e32 v57, 0xffff0000, v57
	v_pk_fma_f32 v[68:69], v[62:63], v[68:69], s[40:41] op_sel_hi:[1,1,0]
	v_pk_mul_f32 v[54:55], v[54:55], 0.5 op_sel_hi:[1,0]
	v_pk_fma_f32 v[68:69], v[62:63], v[68:69], s[42:43] op_sel_hi:[1,1,0]
	v_lshlrev_b32_e32 v52, 16, v53
	v_pk_fma_f32 v[62:63], v[62:63], v[68:69], s[44:45] op_sel_hi:[1,1,0]
	v_and_b32_e32 v53, 0xffff0000, v53
	v_pk_mul_f32 v[58:59], v[58:59], v[62:63]
	v_pk_mul_f32 v[32:33], v[32:33], v[128:129]
	v_pk_fma_f32 v[54:55], v[54:55], v[58:59], v[54:55]
	v_pk_fma_f32 v[56:57], v[86:87], v[56:57], v[98:99]
	v_pk_mul_f32 v[32:33], v[32:33], v[54:55]
	v_lshlrev_b32_e32 v54, 16, v49
	v_and_b32_e32 v55, 0xffff0000, v49
	v_pk_fma_f32 v[52:53], v[90:91], v[52:53], v[56:57]
	v_pk_mul_f32 v[34:35], v[34:35], v[128:129]
	v_pk_fma_f32 v[52:53], v[94:95], v[54:55], v[52:53]
	v_mov_b32_dpp v1, v102 row_ror:1 row_mask:0xf bank_mask:0xf bound_ctrl:1
	v_pk_mul_f32 v[54:55], v[52:53], s[26:27] op_sel_hi:[1,0]
	v_pk_mul_f32 v[52:53], v[52:53], 0.5 op_sel_hi:[1,0]
	v_med3_f32 v54, v54, s71, v224
	v_med3_f32 v55, v55, s71, v224
	v_pk_mul_f32 v[56:57], v[54:55], v[54:55]
	v_mov_b32_dpp v1, v50 row_shr:1 row_mask:0xf bank_mask:0xf
	v_pk_fma_f32 v[58:59], v[56:57], s[28:29], v[2:3] op_sel_hi:[1,0,0] neg_lo:[1,0,0] neg_hi:[1,0,0]
	v_cvt_pk_bf16_f32 v32, v32, v33
	v_pk_mul_f32 v[28:29], v[28:29], v[128:129]
	v_pk_fma_f32 v[58:59], v[56:57], v[58:59], s[34:35] op_sel_hi:[1,1,0]
	v_pk_mul_f32 v[30:31], v[30:31], v[128:129]
	v_pk_fma_f32 v[58:59], v[56:57], v[58:59], s[36:37] op_sel_hi:[1,1,0]
	v_mov_b32_e32 v127, v126
	v_pk_fma_f32 v[58:59], v[56:57], v[58:59], s[38:39] op_sel_hi:[1,1,0]
	v_pk_mul_f32 v[24:25], v[24:25], v[126:127]
	v_pk_fma_f32 v[58:59], v[56:57], v[58:59], s[40:41] op_sel_hi:[1,1,0]
	v_pk_mul_f32 v[26:27], v[26:27], v[126:127]
; __device__ __forceinline__ unsigned cvt_pk_bf16(float lo, float hi) { unsigned r; asm volatile("v_cvt_pk_bf16_f32 %0, %1, %2" : "=v"(r) : "v"(lo), "v"(hi)); return r; }
;     static __device__ __forceinline__ void unpk4(const u32x2 w, float (&o)[4]) { o[0] = bf_lo(w.x); o[1] = bf_hi(w.x); o[2] = bf_lo(w.y); o[3] = bf_hi(w.y); }
;     template <int N> static __device__ __forceinline__ u32x2 dpp_prev(const u32x2 pv, const u32x2 cur) { u32x2 r; r.x = dpp_prev1<N>(pv.x, cur.x); r.y = dpp_prev1<N>(pv.y, cur.y); return r; }
;     static __device__ __forceinline__ u32x2 finish2(const float (&g0)[4], const float (&g1)[4], const float (&g2)[4], const float (&w0)[4], const float (&w1)[4], const float (&w2)[4], const float (&bb)[4],
;                                                     const f32x4 v, float rs) {
;         float h[4];
; #pragma unroll
;         for (int j = 0; j < 4; j += 2) {
;             const f32x2 gc = (f32x2){bb[j] + w0[j] * g2[j] + w1[j] * g1[j] + w2[j] * g0[j], bb[j + 1] + w0[j + 1] * g2[j + 1] + w1[j + 1] * g1[j + 1] + w2[j + 1] * g0[j + 1]};
;             const f32x2 ge = gelu_pk(gc) * ((f32x2){v[j], v[j + 1]} * rs); h[j] = ge.x; h[j + 1] = ge.y; }
;         u32x2 w; w.x = cvt_pk_bf16(h[0], h[1]); w.y = cvt_pk_bf16(h[2], h[3]); return w;
;     __device__ __forceinline__ void operator()(const f32x4 (&acc)[2][2][4][2], const Unit& u, int wr, int wc, int fr, int fq) const {
;     ...
;                 for (int m = 0; m < 4; ++m) { const u32x4 cur = gq[m]; u32x4 hw;
; #pragma unroll
;                     for (int hv = 0; hv < 2; ++hv) { const u32x2 c2 = half2(cur, hv), p2 = half2(pv, hv);
;                         const u32x2 q1 = dpp_prev<1>(p2, c2), q2 = dpp_prev<2>(p2, c2);
;                         float g0[4], g1[4], g2[4]; unpk4(c2, g0); unpk4(q1, g1); unpk4(q2, g2);
;                         const u32x2 r = finish2(g0, g1, g2, w0[hv], w1[hv], w2[hv], bb[hv], acc[ai][bj][m][hv], rs8[ai][m]);
;                         if (hv == 0) { hw.x = r.x; hw.y = r.y; } else { hw.z = r.x; hw.w = r.y; } }
;                     *(u32x4*)(H + (size_t)(R0 + fr + 16 * m) * 2816 + col8) = hw;
	v_pk_fma_f32 v[58:59], v[56:57], v[58:59], s[42:43] op_sel_hi:[1,1,0]
	v_pk_mul_f32 v[20:21], v[20:21], v[126:127]
	v_pk_fma_f32 v[56:57], v[56:57], v[58:59], s[44:45] op_sel_hi:[1,1,0]
	v_lshlrev_b32_e32 v58, 16, v50
	v_pk_mul_f32 v[54:55], v[54:55], v[56:57]
	v_and_b32_e32 v59, 0xffff0000, v50
	v_pk_fma_f32 v[52:53], v[52:53], v[54:55], v[52:53]
	v_mov_b32_dpp v55, v102 row_ror:2 row_mask:0xf bank_mask:0xf bound_ctrl:1
	v_pk_mul_f32 v[34:35], v[34:35], v[52:53]
	v_mov_b32_dpp v57, v103 row_ror:2 row_mask:0xf bank_mask:0xf bound_ctrl:1
	v_mov_b32_dpp v55, v50 row_shr:2 row_mask:0xf bank_mask:0xf
	v_lshlrev_b32_e32 v54, 16, v55
	v_and_b32_e32 v55, 0xffff0000, v55
	v_cvt_pk_bf16_f32 v33, v34, v35
	v_lshlrev_b32_e32 v34, 16, v1
	v_and_b32_e32 v35, 0xffff0000, v1
	v_pk_fma_f32 v[54:55], v[64:65], v[54:55], v[80:81]
	v_mov_b32_dpp v53, v103 row_ror:1 row_mask:0xf bank_mask:0xf bound_ctrl:1
	v_pk_fma_f32 v[34:35], v[72:73], v[34:35], v[54:55]
	v_mov_b32_dpp v57, v51 row_shr:2 row_mask:0xf bank_mask:0xf
	v_pk_fma_f32 v[34:35], v[76:77], v[58:59], v[34:35]
	v_mov_b32_dpp v53, v51 row_shr:1 row_mask:0xf bank_mask:0xf
	v_pk_mul_f32 v[54:55], v[34:35], s[26:27] op_sel_hi:[1,0]
	v_lshlrev_b32_e32 v56, 16, v57
	v_med3_f32 v54, v54, s71, v224
	v_med3_f32 v55, v55, s71, v224
	v_pk_mul_f32 v[58:59], v[54:55], v[54:55]
	v_and_b32_e32 v57, 0xffff0000, v57
	v_pk_fma_f32 v[62:63], v[58:59], s[28:29], v[2:3] op_sel_hi:[1,0,0] neg_lo:[1,0,0] neg_hi:[1,0,0]
	v_pk_mul_f32 v[34:35], v[34:35], 0.5 op_sel_hi:[1,0]
	v_pk_fma_f32 v[62:63], v[58:59], v[62:63], s[34:35] op_sel_hi:[1,1,0]
	v_lshlrev_b32_e32 v52, 16, v53
	v_pk_fma_f32 v[62:63], v[58:59], v[62:63], s[36:37] op_sel_hi:[1,1,0]
	v_and_b32_e32 v53, 0xffff0000, v53
	v_pk_fma_f32 v[62:63], v[58:59], v[62:63], s[38:39] op_sel_hi:[1,1,0]
	v_mov_b32_dpp v1, v48 row_ror:1 row_mask:0xf bank_mask:0xf bound_ctrl:1
	v_pk_fma_f32 v[62:63], v[58:59], v[62:63], s[40:41] op_sel_hi:[1,1,0]
	v_pk_mul_f32 v[22:23], v[22:23], v[126:127]
	v_pk_fma_f32 v[62:63], v[58:59], v[62:63], s[42:43] op_sel_hi:[1,1,0]
	v_mov_b32_dpp v1, v44 row_shr:1 row_mask:0xf bank_mask:0xf
	v_pk_fma_f32 v[58:59], v[58:59], v[62:63], s[44:45] op_sel_hi:[1,1,0]
	v_mov_b32_e32 v125, v124
	v_pk_mul_f32 v[54:55], v[54:55], v[58:59]
	v_pk_mul_f32 v[16:17], v[16:17], v[124:125]
	v_pk_fma_f32 v[34:35], v[34:35], v[54:55], v[34:35]
	v_pk_fma_f32 v[54:55], v[66:67], v[56:57], v[82:83]
	v_pk_mul_f32 v[28:29], v[28:29], v[34:35]
	v_lshlrev_b32_e32 v34, 16, v51
	v_and_b32_e32 v35, 0xffff0000, v51
	v_pk_fma_f32 v[52:53], v[74:75], v[52:53], v[54:55]
	v_pk_mul_f32 v[18:19], v[18:19], v[124:125]
	v_pk_fma_f32 v[34:35], v[78:79], v[34:35], v[52:53]
	v_pk_mul_f32 v[12:13], v[12:13], v[124:125]
	v_pk_mul_f32 v[52:53], v[34:35], s[26:27] op_sel_hi:[1,0]
	v_pk_mul_f32 v[34:35], v[34:35], 0.5 op_sel_hi:[1,0]
	v_med3_f32 v52, v52, s71, v224
	v_med3_f32 v53, v53, s71, v224
	v_pk_mul_f32 v[54:55], v[52:53], v[52:53]
	v_pk_mul_f32 v[14:15], v[14:15], v[124:125]
	v_pk_fma_f32 v[56:57], v[54:55], s[28:29], v[2:3] op_sel_hi:[1,0,0] neg_lo:[1,0,0] neg_hi:[1,0,0]
	v_mov_b32_e32 v123, v122
	v_pk_fma_f32 v[56:57], v[54:55], v[56:57], s[34:35] op_sel_hi:[1,1,0]
	v_pk_mul_f32 v[8:9], v[8:9], v[122:123]
	v_pk_fma_f32 v[56:57], v[54:55], v[56:57], s[36:37] op_sel_hi:[1,1,0]
	v_pk_mul_f32 v[10:11], v[10:11], v[122:123]
	v_pk_fma_f32 v[56:57], v[54:55], v[56:57], s[38:39] op_sel_hi:[1,1,0]
	v_pk_mul_f32 v[4:5], v[4:5], v[122:123]
	v_pk_fma_f32 v[56:57], v[54:55], v[56:57], s[40:41] op_sel_hi:[1,1,0]
	v_pk_mul_f32 v[6:7], v[6:7], v[122:123]
	v_pk_fma_f32 v[56:57], v[54:55], v[56:57], s[42:43] op_sel_hi:[1,1,0]
	s_nop 0
	v_pk_fma_f32 v[54:55], v[54:55], v[56:57], s[44:45] op_sel_hi:[1,1,0]
	s_nop 0
	v_pk_mul_f32 v[52:53], v[52:53], v[54:55]
	s_nop 0
	v_pk_fma_f32 v[34:35], v[34:35], v[52:53], v[34:35]
	s_nop 0
	v_pk_mul_f32 v[30:31], v[30:31], v[34:35]
	v_cvt_pk_bf16_f32 v34, v28, v29
	v_lshl_add_u64 v[28:29], v[168:169], 0, v[60:61]
	v_cvt_pk_bf16_f32 v35, v30, v31
	global_store_dwordx4 v[28:29], v[32:35], off sc1
	v_lshlrev_b32_e32 v28, 16, v1
	v_and_b32_e32 v29, 0xffff0000, v1
	v_mov_b32_dpp v33, v48 row_ror:2 row_mask:0xf bank_mask:0xf bound_ctrl:1
	v_mov_b32_dpp v31, v49 row_ror:1 row_mask:0xf bank_mask:0xf bound_ctrl:1
	v_mov_b32_dpp v35, v49 row_ror:2 row_mask:0xf bank_mask:0xf bound_ctrl:1
	v_mov_b32_dpp v33, v44 row_shr:2 row_mask:0xf bank_mask:0xf
	v_lshlrev_b32_e32 v32, 16, v33
	v_and_b32_e32 v33, 0xffff0000, v33
	v_pk_fma_f32 v[32:33], v[84:85], v[32:33], v[96:97]
	v_lshlrev_b32_e32 v48, 16, v44
	v_and_b32_e32 v49, 0xffff0000, v44
	v_pk_fma_f32 v[28:29], v[88:89], v[28:29], v[32:33]
	v_mov_b32_dpp v35, v45 row_shr:2 row_mask:0xf bank_mask:0xf
	v_pk_fma_f32 v[28:29], v[92:93], v[48:49], v[28:29]
	v_mov_b32_dpp v31, v45 row_shr:1 row_mask:0xf bank_mask:0xf
	v_pk_mul_f32 v[32:33], v[28:29], s[26:27] op_sel_hi:[1,0]
	v_lshlrev_b32_e32 v34, 16, v35
	v_med3_f32 v32, v32, s71, v224
	v_med3_f32 v33, v33, s71, v224
	v_pk_mul_f32 v[48:49], v[32:33], v[32:33]
	v_and_b32_e32 v35, 0xffff0000, v35
	v_pk_fma_f32 v[52:53], v[48:49], s[28:29], v[2:3] op_sel_hi:[1,0,0] neg_lo:[1,0,0] neg_hi:[1,0,0]
	v_pk_mul_f32 v[28:29], v[28:29], 0.5 op_sel_hi:[1,0]
	v_pk_fma_f32 v[52:53], v[48:49], v[52:53], s[34:35] op_sel_hi:[1,1,0]
	v_lshlrev_b32_e32 v30, 16, v31
	v_pk_fma_f32 v[52:53], v[48:49], v[52:53], s[36:37] op_sel_hi:[1,1,0]
	v_and_b32_e32 v31, 0xffff0000, v31
	v_pk_fma_f32 v[52:53], v[48:49], v[52:53], s[38:39] op_sel_hi:[1,1,0]
	v_mov_b32_dpp v1, v50 row_ror:1 row_mask:0xf bank_mask:0xf bound_ctrl:1
	v_pk_fma_f32 v[52:53], v[48:49], v[52:53], s[40:41] op_sel_hi:[1,1,0]
	s_nop 0
; __device__ __forceinline__ unsigned cvt_pk_bf16(float lo, float hi) { unsigned r; asm volatile("v_cvt_pk_bf16_f32 %0, %1, %2" : "=v"(r) : "v"(lo), "v"(hi)); return r; }
;     static __device__ __forceinline__ void unpk4(const u32x2 w, float (&o)[4]) { o[0] = bf_lo(w.x); o[1] = bf_hi(w.x); o[2] = bf_lo(w.y); o[3] = bf_hi(w.y); }
;     template <int N> static __device__ __forceinline__ u32x2 dpp_prev(const u32x2 pv, const u32x2 cur) { u32x2 r; r.x = dpp_prev1<N>(pv.x, cur.x); r.y = dpp_prev1<N>(pv.y, cur.y); return r; }
;     static __device__ __forceinline__ u32x2 finish2(const float (&g0)[4], const float (&g1)[4], const float (&g2)[4], const float (&w0)[4], const float (&w1)[4], const float (&w2)[4], const float (&bb)[4],
;                                                     const f32x4 v, float rs) {
;         float h[4];
; #pragma unroll
;         for (int j = 0; j < 4; j += 2) {
;             const f32x2 gc = (f32x2){bb[j] + w0[j] * g2[j] + w1[j] * g1[j] + w2[j] * g0[j], bb[j + 1] + w0[j + 1] * g2[j + 1] + w1[j + 1] * g1[j + 1] + w2[j + 1] * g0[j + 1]};
;             const f32x2 ge = gelu_pk(gc) * ((f32x2){v[j], v[j + 1]} * rs); h[j] = ge.x; h[j + 1] = ge.y; }
;         u32x2 w; w.x = cvt_pk_bf16(h[0], h[1]); w.y = cvt_pk_bf16(h[2], h[3]); return w;
;     __device__ __forceinline__ void operator()(const f32x4 (&acc)[2][2][4][2], const Unit& u, int wr, int wc, int fr, int fq) const {
;     ...
;                 for (int m = 0; m < 4; ++m) { const u32x4 cur = gq[m]; u32x4 hw;
; #pragma unroll
;                     for (int hv = 0; hv < 2; ++hv) { const u32x2 c2 = half2(cur, hv), p2 = half2(pv, hv);
;                         const u32x2 q1 = dpp_prev<1>(p2, c2), q2 = dpp_prev<2>(p2, c2);
;                         float g0[4], g1[4], g2[4]; unpk4(c2, g0); unpk4(q1, g1); unpk4(q2, g2);
;                         const u32x2 r = finish2(g0, g1, g2, w0[hv], w1[hv], w2[hv], bb[hv], acc[ai][bj][m][hv], rs8[ai][m]);
;                         if (hv == 0) { hw.x = r.x; hw.y = r.y; } else { hw.z = r.x; hw.w = r.y; } }
;                     *(u32x4*)(H + (size_t)(R0 + fr + 16 * m) * 2816 + col8) = hw;
	v_pk_fma_f32 v[52:53], v[48:49], v[52:53], s[42:43] op_sel_hi:[1,1,0]
	v_mov_b32_dpp v1, v46 row_shr:1 row_mask:0xf bank_mask:0xf
	v_pk_fma_f32 v[48:49], v[48:49], v[52:53], s[44:45] op_sel_hi:[1,1,0]
	s_nop 0
	v_pk_mul_f32 v[32:33], v[32:33], v[48:49]
	s_nop 0
	v_pk_fma_f32 v[28:29], v[28:29], v[32:33], v[28:29]
	v_pk_fma_f32 v[32:33], v[86:87], v[34:35], v[98:99]
	v_pk_mul_f32 v[24:25], v[24:25], v[28:29]
	v_lshlrev_b32_e32 v28, 16, v45
	v_and_b32_e32 v29, 0xffff0000, v45
	v_pk_fma_f32 v[30:31], v[90:91], v[30:31], v[32:33]
	v_cvt_pk_bf16_f32 v24, v24, v25
	s_nop 0
	v_pk_fma_f32 v[28:29], v[94:95], v[28:29], v[30:31]
	s_nop 0
	v_pk_mul_f32 v[30:31], v[28:29], s[26:27] op_sel_hi:[1,0]
	v_pk_mul_f32 v[28:29], v[28:29], 0.5 op_sel_hi:[1,0]
	v_med3_f32 v30, v30, s71, v224
	v_med3_f32 v31, v31, s71, v224
	v_pk_mul_f32 v[32:33], v[30:31], v[30:31]
	s_nop 0
	v_pk_fma_f32 v[34:35], v[32:33], s[28:29], v[2:3] op_sel_hi:[1,0,0] neg_lo:[1,0,0] neg_hi:[1,0,0]
	s_nop 0
	v_pk_fma_f32 v[34:35], v[32:33], v[34:35], s[34:35] op_sel_hi:[1,1,0]
	s_nop 0
	v_pk_fma_f32 v[34:35], v[32:33], v[34:35], s[36:37] op_sel_hi:[1,1,0]
	s_nop 0
	v_pk_fma_f32 v[34:35], v[32:33], v[34:35], s[38:39] op_sel_hi:[1,1,0]
	s_nop 0
	v_pk_fma_f32 v[34:35], v[32:33], v[34:35], s[40:41] op_sel_hi:[1,1,0]
	s_nop 0
	v_pk_fma_f32 v[34:35], v[32:33], v[34:35], s[42:43] op_sel_hi:[1,1,0]
	s_nop 0
	v_pk_fma_f32 v[32:33], v[32:33], v[34:35], s[44:45] op_sel_hi:[1,1,0]
	v_lshlrev_b32_e32 v34, 16, v46
	v_pk_mul_f32 v[30:31], v[30:31], v[32:33]
	v_and_b32_e32 v35, 0xffff0000, v46
	v_pk_fma_f32 v[28:29], v[28:29], v[30:31], v[28:29]
	v_mov_b32_dpp v31, v50 row_ror:2 row_mask:0xf bank_mask:0xf bound_ctrl:1
	v_pk_mul_f32 v[26:27], v[26:27], v[28:29]
	v_mov_b32_dpp v33, v51 row_ror:2 row_mask:0xf bank_mask:0xf bound_ctrl:1
	v_mov_b32_dpp v31, v46 row_shr:2 row_mask:0xf bank_mask:0xf
	v_lshlrev_b32_e32 v30, 16, v31
	v_and_b32_e32 v31, 0xffff0000, v31
	v_cvt_pk_bf16_f32 v25, v26, v27
	v_lshlrev_b32_e32 v26, 16, v1
	v_and_b32_e32 v27, 0xffff0000, v1
	v_pk_fma_f32 v[30:31], v[64:65], v[30:31], v[80:81]
	v_mov_b32_dpp v29, v51 row_ror:1 row_mask:0xf bank_mask:0xf bound_ctrl:1
	v_pk_fma_f32 v[26:27], v[72:73], v[26:27], v[30:31]
	v_mov_b32_dpp v33, v47 row_shr:2 row_mask:0xf bank_mask:0xf
	v_pk_fma_f32 v[26:27], v[76:77], v[34:35], v[26:27]
	v_mov_b32_dpp v29, v47 row_shr:1 row_mask:0xf bank_mask:0xf
	v_pk_mul_f32 v[30:31], v[26:27], s[26:27] op_sel_hi:[1,0]
	v_lshlrev_b32_e32 v32, 16, v33
	v_med3_f32 v30, v30, s71, v224
	v_med3_f32 v31, v31, s71, v224
	v_pk_mul_f32 v[34:35], v[30:31], v[30:31]
	v_and_b32_e32 v33, 0xffff0000, v33
	v_pk_fma_f32 v[48:49], v[34:35], s[28:29], v[2:3] op_sel_hi:[1,0,0] neg_lo:[1,0,0] neg_hi:[1,0,0]
	v_pk_mul_f32 v[26:27], v[26:27], 0.5 op_sel_hi:[1,0]
	v_pk_fma_f32 v[48:49], v[34:35], v[48:49], s[34:35] op_sel_hi:[1,1,0]
	v_lshlrev_b32_e32 v28, 16, v29
	v_pk_fma_f32 v[48:49], v[34:35], v[48:49], s[36:37] op_sel_hi:[1,1,0]
	v_and_b32_e32 v29, 0xffff0000, v29
	v_pk_fma_f32 v[48:49], v[34:35], v[48:49], s[38:39] op_sel_hi:[1,1,0]
	v_mov_b32_dpp v1, v44 row_ror:1 row_mask:0xf bank_mask:0xf bound_ctrl:1
	v_pk_fma_f32 v[48:49], v[34:35], v[48:49], s[40:41] op_sel_hi:[1,1,0]
	s_nop 0
	v_pk_fma_f32 v[48:49], v[34:35], v[48:49], s[42:43] op_sel_hi:[1,1,0]
	v_mov_b32_dpp v1, v40 row_shr:1 row_mask:0xf bank_mask:0xf
	v_pk_fma_f32 v[34:35], v[34:35], v[48:49], s[44:45] op_sel_hi:[1,1,0]
	s_nop 0
	v_pk_mul_f32 v[30:31], v[30:31], v[34:35]
	s_nop 0
	v_pk_fma_f32 v[26:27], v[26:27], v[30:31], v[26:27]
	v_pk_fma_f32 v[30:31], v[66:67], v[32:33], v[82:83]
	v_pk_mul_f32 v[20:21], v[20:21], v[26:27]
	v_lshlrev_b32_e32 v26, 16, v47
	v_and_b32_e32 v27, 0xffff0000, v47
	v_pk_fma_f32 v[28:29], v[74:75], v[28:29], v[30:31]
	s_nop 0
	v_pk_fma_f32 v[26:27], v[78:79], v[26:27], v[28:29]
	s_nop 0
	v_pk_mul_f32 v[28:29], v[26:27], s[26:27] op_sel_hi:[1,0]
	v_pk_mul_f32 v[26:27], v[26:27], 0.5 op_sel_hi:[1,0]
	v_med3_f32 v28, v28, s71, v224
	v_med3_f32 v29, v29, s71, v224
	v_pk_mul_f32 v[30:31], v[28:29], v[28:29]
	s_nop 0
	v_pk_fma_f32 v[32:33], v[30:31], s[28:29], v[2:3] op_sel_hi:[1,0,0] neg_lo:[1,0,0] neg_hi:[1,0,0]
	s_nop 0
	v_pk_fma_f32 v[32:33], v[30:31], v[32:33], s[34:35] op_sel_hi:[1,1,0]
	s_nop 0
	v_pk_fma_f32 v[32:33], v[30:31], v[32:33], s[36:37] op_sel_hi:[1,1,0]
	s_nop 0
	v_pk_fma_f32 v[32:33], v[30:31], v[32:33], s[38:39] op_sel_hi:[1,1,0]
	s_nop 0
	v_pk_fma_f32 v[32:33], v[30:31], v[32:33], s[40:41] op_sel_hi:[1,1,0]
	s_nop 0
	v_pk_fma_f32 v[32:33], v[30:31], v[32:33], s[42:43] op_sel_hi:[1,1,0]
	s_nop 0
	v_pk_fma_f32 v[30:31], v[30:31], v[32:33], s[44:45] op_sel_hi:[1,1,0]
	s_nop 0
	v_pk_mul_f32 v[28:29], v[28:29], v[30:31]
	s_nop 0
	v_pk_fma_f32 v[26:27], v[26:27], v[28:29], v[26:27]
	v_lshlrev_b32_e32 v28, 16, v40
	v_pk_mul_f32 v[22:23], v[22:23], v[26:27]
	v_cvt_pk_bf16_f32 v26, v20, v21
	v_lshl_add_u64 v[20:21], v[170:171], 0, v[60:61]
	v_cvt_pk_bf16_f32 v27, v22, v23
	global_store_dwordx4 v[20:21], v[24:27], off sc1
	v_lshlrev_b32_e32 v20, 16, v1
	v_and_b32_e32 v21, 0xffff0000, v1
	v_mov_b32_dpp v25, v44 row_ror:2 row_mask:0xf bank_mask:0xf bound_ctrl:1
	v_and_b32_e32 v29, 0xffff0000, v40
	v_mov_b32_dpp v27, v45 row_ror:2 row_mask:0xf bank_mask:0xf bound_ctrl:1
	v_mov_b32_dpp v25, v40 row_shr:2 row_mask:0xf bank_mask:0xf
	v_lshlrev_b32_e32 v24, 16, v25
	v_and_b32_e32 v25, 0xffff0000, v25
	v_pk_fma_f32 v[24:25], v[84:85], v[24:25], v[96:97]
	v_mov_b32_dpp v23, v45 row_ror:1 row_mask:0xf bank_mask:0xf bound_ctrl:1
	v_pk_fma_f32 v[20:21], v[88:89], v[20:21], v[24:25]
	v_mov_b32_dpp v27, v41 row_shr:2 row_mask:0xf bank_mask:0xf
	v_pk_fma_f32 v[20:21], v[92:93], v[28:29], v[20:21]
; __device__ __forceinline__ unsigned cvt_pk_bf16(float lo, float hi) { unsigned r; asm volatile("v_cvt_pk_bf16_f32 %0, %1, %2" : "=v"(r) : "v"(lo), "v"(hi)); return r; }
;     static __device__ __forceinline__ void unpk4(const u32x2 w, float (&o)[4]) { o[0] = bf_lo(w.x); o[1] = bf_hi(w.x); o[2] = bf_lo(w.y); o[3] = bf_hi(w.y); }
;     template <int N> static __device__ __forceinline__ u32x2 dpp_prev(const u32x2 pv, const u32x2 cur) { u32x2 r; r.x = dpp_prev1<N>(pv.x, cur.x); r.y = dpp_prev1<N>(pv.y, cur.y); return r; }
;     static __device__ __forceinline__ u32x2 finish2(const float (&g0)[4], const float (&g1)[4], const float (&g2)[4], const float (&w0)[4], const float (&w1)[4], const float (&w2)[4], const float (&bb)[4],
;                                                     const f32x4 v, float rs) {
;         float h[4];
; #pragma unroll
;         for (int j = 0; j < 4; j += 2) {
;             const f32x2 gc = (f32x2){bb[j] + w0[j] * g2[j] + w1[j] * g1[j] + w2[j] * g0[j], bb[j + 1] + w0[j + 1] * g2[j + 1] + w1[j + 1] * g1[j + 1] + w2[j + 1] * g0[j + 1]};
;             const f32x2 ge = gelu_pk(gc) * ((f32x2){v[j], v[j + 1]} * rs); h[j] = ge.x; h[j + 1] = ge.y; }
;         u32x2 w; w.x = cvt_pk_bf16(h[0], h[1]); w.y = cvt_pk_bf16(h[2], h[3]); return w;
;     __device__ __forceinline__ void operator()(const f32x4 (&acc)[2][2][4][2], const Unit& u, int wr, int wc, int fr, int fq) const {
;     ...
;                 for (int m = 0; m < 4; ++m) { const u32x4 cur = gq[m]; u32x4 hw;
; #pragma unroll
;                     for (int hv = 0; hv < 2; ++hv) { const u32x2 c2 = half2(cur, hv), p2 = half2(pv, hv);
;                         const u32x2 q1 = dpp_prev<1>(p2, c2), q2 = dpp_prev<2>(p2, c2);
;                         float g0[4], g1[4], g2[4]; unpk4(c2, g0); unpk4(q1, g1); unpk4(q2, g2);
;                         const u32x2 r = finish2(g0, g1, g2, w0[hv], w1[hv], w2[hv], bb[hv], acc[ai][bj][m][hv], rs8[ai][m]);
;                         if (hv == 0) { hw.x = r.x; hw.y = r.y; } else { hw.z = r.x; hw.w = r.y; } }
;                     *(u32x4*)(H + (size_t)(R0 + fr + 16 * m) * 2816 + col8) = hw;
	v_mov_b32_dpp v23, v41 row_shr:1 row_mask:0xf bank_mask:0xf
	v_pk_mul_f32 v[24:25], v[20:21], s[26:27] op_sel_hi:[1,0]
	v_lshlrev_b32_e32 v26, 16, v27
	v_med3_f32 v24, v24, s71, v224
	v_med3_f32 v25, v25, s71, v224
	v_pk_mul_f32 v[28:29], v[24:25], v[24:25]
	v_and_b32_e32 v27, 0xffff0000, v27
	v_pk_fma_f32 v[30:31], v[28:29], s[28:29], v[2:3] op_sel_hi:[1,0,0] neg_lo:[1,0,0] neg_hi:[1,0,0]
	v_pk_mul_f32 v[20:21], v[20:21], 0.5 op_sel_hi:[1,0]
	v_pk_fma_f32 v[30:31], v[28:29], v[30:31], s[34:35] op_sel_hi:[1,1,0]
	v_lshlrev_b32_e32 v22, 16, v23
	v_pk_fma_f32 v[30:31], v[28:29], v[30:31], s[36:37] op_sel_hi:[1,1,0]
	v_and_b32_e32 v23, 0xffff0000, v23
	v_pk_fma_f32 v[30:31], v[28:29], v[30:31], s[38:39] op_sel_hi:[1,1,0]
	v_mov_b32_dpp v1, v46 row_ror:1 row_mask:0xf bank_mask:0xf bound_ctrl:1
	v_pk_fma_f32 v[30:31], v[28:29], v[30:31], s[40:41] op_sel_hi:[1,1,0]
	s_nop 0
	v_pk_fma_f32 v[30:31], v[28:29], v[30:31], s[42:43] op_sel_hi:[1,1,0]
	v_mov_b32_dpp v1, v42 row_shr:1 row_mask:0xf bank_mask:0xf
	v_pk_fma_f32 v[28:29], v[28:29], v[30:31], s[44:45] op_sel_hi:[1,1,0]
	s_nop 0
	v_pk_mul_f32 v[24:25], v[24:25], v[28:29]
	s_nop 0
	v_pk_fma_f32 v[20:21], v[20:21], v[24:25], v[20:21]
	v_pk_fma_f32 v[24:25], v[86:87], v[26:27], v[98:99]
	v_pk_mul_f32 v[16:17], v[16:17], v[20:21]
	v_lshlrev_b32_e32 v20, 16, v41
	v_and_b32_e32 v21, 0xffff0000, v41
	v_pk_fma_f32 v[22:23], v[90:91], v[22:23], v[24:25]
	v_cvt_pk_bf16_f32 v16, v16, v17
	s_nop 0
	v_pk_fma_f32 v[20:21], v[94:95], v[20:21], v[22:23]
	s_nop 0
	v_pk_mul_f32 v[22:23], v[20:21], s[26:27] op_sel_hi:[1,0]
	v_pk_mul_f32 v[20:21], v[20:21], 0.5 op_sel_hi:[1,0]
	v_med3_f32 v22, v22, s71, v224
	v_med3_f32 v23, v23, s71, v224
	v_pk_mul_f32 v[24:25], v[22:23], v[22:23]
	s_nop 0
	v_pk_fma_f32 v[26:27], v[24:25], s[28:29], v[2:3] op_sel_hi:[1,0,0] neg_lo:[1,0,0] neg_hi:[1,0,0]
	s_nop 0
	v_pk_fma_f32 v[26:27], v[24:25], v[26:27], s[34:35] op_sel_hi:[1,1,0]
	s_nop 0
	v_pk_fma_f32 v[26:27], v[24:25], v[26:27], s[36:37] op_sel_hi:[1,1,0]
	s_nop 0
	v_pk_fma_f32 v[26:27], v[24:25], v[26:27], s[38:39] op_sel_hi:[1,1,0]
	s_nop 0
	v_pk_fma_f32 v[26:27], v[24:25], v[26:27], s[40:41] op_sel_hi:[1,1,0]
	s_nop 0
	v_pk_fma_f32 v[26:27], v[24:25], v[26:27], s[42:43] op_sel_hi:[1,1,0]
	s_nop 0
	v_pk_fma_f32 v[24:25], v[24:25], v[26:27], s[44:45] op_sel_hi:[1,1,0]
	v_lshlrev_b32_e32 v26, 16, v42
	v_pk_mul_f32 v[22:23], v[22:23], v[24:25]
	v_and_b32_e32 v27, 0xffff0000, v42
	v_pk_fma_f32 v[20:21], v[20:21], v[22:23], v[20:21]
	v_mov_b32_dpp v23, v46 row_ror:2 row_mask:0xf bank_mask:0xf bound_ctrl:1
	v_pk_mul_f32 v[18:19], v[18:19], v[20:21]
	v_mov_b32_dpp v25, v47 row_ror:2 row_mask:0xf bank_mask:0xf bound_ctrl:1
	v_mov_b32_dpp v23, v42 row_shr:2 row_mask:0xf bank_mask:0xf
	v_lshlrev_b32_e32 v22, 16, v23
	v_and_b32_e32 v23, 0xffff0000, v23
	v_cvt_pk_bf16_f32 v17, v18, v19
	v_lshlrev_b32_e32 v18, 16, v1
	v_and_b32_e32 v19, 0xffff0000, v1
	v_pk_fma_f32 v[22:23], v[64:65], v[22:23], v[80:81]
	v_mov_b32_dpp v21, v47 row_ror:1 row_mask:0xf bank_mask:0xf bound_ctrl:1
	v_pk_fma_f32 v[18:19], v[72:73], v[18:19], v[22:23]
	v_mov_b32_dpp v25, v43 row_shr:2 row_mask:0xf bank_mask:0xf
	v_pk_fma_f32 v[18:19], v[76:77], v[26:27], v[18:19]
	v_mov_b32_dpp v21, v43 row_shr:1 row_mask:0xf bank_mask:0xf
	v_pk_mul_f32 v[22:23], v[18:19], s[26:27] op_sel_hi:[1,0]
	v_lshlrev_b32_e32 v24, 16, v25
	v_med3_f32 v22, v22, s71, v224
	v_med3_f32 v23, v23, s71, v224
	v_pk_mul_f32 v[26:27], v[22:23], v[22:23]
	v_and_b32_e32 v25, 0xffff0000, v25
	v_pk_fma_f32 v[28:29], v[26:27], s[28:29], v[2:3] op_sel_hi:[1,0,0] neg_lo:[1,0,0] neg_hi:[1,0,0]
	v_pk_mul_f32 v[18:19], v[18:19], 0.5 op_sel_hi:[1,0]
	v_pk_fma_f32 v[28:29], v[26:27], v[28:29], s[34:35] op_sel_hi:[1,1,0]
	v_lshlrev_b32_e32 v20, 16, v21
	v_pk_fma_f32 v[28:29], v[26:27], v[28:29], s[36:37] op_sel_hi:[1,1,0]
	v_and_b32_e32 v21, 0xffff0000, v21
	v_pk_fma_f32 v[28:29], v[26:27], v[28:29], s[38:39] op_sel_hi:[1,1,0]
	v_mov_b32_dpp v1, v40 row_ror:1 row_mask:0xf bank_mask:0xf bound_ctrl:1
	v_pk_fma_f32 v[28:29], v[26:27], v[28:29], s[40:41] op_sel_hi:[1,1,0]
	s_nop 0
	v_pk_fma_f32 v[28:29], v[26:27], v[28:29], s[42:43] op_sel_hi:[1,1,0]
	v_mov_b32_dpp v1, v36 row_shr:1 row_mask:0xf bank_mask:0xf
	v_pk_fma_f32 v[26:27], v[26:27], v[28:29], s[44:45] op_sel_hi:[1,1,0]
	s_nop 0
	v_pk_mul_f32 v[22:23], v[22:23], v[26:27]
	s_nop 0
	v_pk_fma_f32 v[18:19], v[18:19], v[22:23], v[18:19]
	v_pk_fma_f32 v[22:23], v[66:67], v[24:25], v[82:83]
	v_pk_mul_f32 v[12:13], v[12:13], v[18:19]
	v_lshlrev_b32_e32 v18, 16, v43
	v_and_b32_e32 v19, 0xffff0000, v43
	v_pk_fma_f32 v[20:21], v[74:75], v[20:21], v[22:23]
	s_nop 0
	v_pk_fma_f32 v[18:19], v[78:79], v[18:19], v[20:21]
	s_nop 0
	v_pk_mul_f32 v[20:21], v[18:19], s[26:27] op_sel_hi:[1,0]
	v_pk_mul_f32 v[18:19], v[18:19], 0.5 op_sel_hi:[1,0]
	v_med3_f32 v20, v20, s71, v224
	v_med3_f32 v21, v21, s71, v224
	v_pk_mul_f32 v[22:23], v[20:21], v[20:21]
	s_nop 0
	v_pk_fma_f32 v[24:25], v[22:23], s[28:29], v[2:3] op_sel_hi:[1,0,0] neg_lo:[1,0,0] neg_hi:[1,0,0]
	s_nop 0
	v_pk_fma_f32 v[24:25], v[22:23], v[24:25], s[34:35] op_sel_hi:[1,1,0]
	s_nop 0
	v_pk_fma_f32 v[24:25], v[22:23], v[24:25], s[36:37] op_sel_hi:[1,1,0]
	s_nop 0
	v_pk_fma_f32 v[24:25], v[22:23], v[24:25], s[38:39] op_sel_hi:[1,1,0]
	s_nop 0
	v_pk_fma_f32 v[24:25], v[22:23], v[24:25], s[40:41] op_sel_hi:[1,1,0]
	s_nop 0
	v_pk_fma_f32 v[24:25], v[22:23], v[24:25], s[42:43] op_sel_hi:[1,1,0]
	s_nop 0
	v_pk_fma_f32 v[22:23], v[22:23], v[24:25], s[44:45] op_sel_hi:[1,1,0]
	s_nop 0
	v_pk_mul_f32 v[20:21], v[20:21], v[22:23]
	s_nop 0
	v_pk_fma_f32 v[18:19], v[18:19], v[20:21], v[18:19]
	v_lshlrev_b32_e32 v20, 16, v36
; __device__ __forceinline__ unsigned cvt_pk_bf16(float lo, float hi) { unsigned r; asm volatile("v_cvt_pk_bf16_f32 %0, %1, %2" : "=v"(r) : "v"(lo), "v"(hi)); return r; }
;     static __device__ __forceinline__ void unpk4(const u32x2 w, float (&o)[4]) { o[0] = bf_lo(w.x); o[1] = bf_hi(w.x); o[2] = bf_lo(w.y); o[3] = bf_hi(w.y); }
;     template <int N> static __device__ __forceinline__ u32x2 dpp_prev(const u32x2 pv, const u32x2 cur) { u32x2 r; r.x = dpp_prev1<N>(pv.x, cur.x); r.y = dpp_prev1<N>(pv.y, cur.y); return r; }
;     static __device__ __forceinline__ u32x2 finish2(const float (&g0)[4], const float (&g1)[4], const float (&g2)[4], const float (&w0)[4], const float (&w1)[4], const float (&w2)[4], const float (&bb)[4],
;                                                     const f32x4 v, float rs) {
;         float h[4];
; #pragma unroll
;         for (int j = 0; j < 4; j += 2) {
;             const f32x2 gc = (f32x2){bb[j] + w0[j] * g2[j] + w1[j] * g1[j] + w2[j] * g0[j], bb[j + 1] + w0[j + 1] * g2[j + 1] + w1[j + 1] * g1[j + 1] + w2[j + 1] * g0[j + 1]};
;             const f32x2 ge = gelu_pk(gc) * ((f32x2){v[j], v[j + 1]} * rs); h[j] = ge.x; h[j + 1] = ge.y; }
;         u32x2 w; w.x = cvt_pk_bf16(h[0], h[1]); w.y = cvt_pk_bf16(h[2], h[3]); return w;
;     __device__ __forceinline__ void operator()(const f32x4 (&acc)[2][2][4][2], const Unit& u, int wr, int wc, int fr, int fq) const {
;     ...
;                 for (int m = 0; m < 4; ++m) { const u32x4 cur = gq[m]; u32x4 hw;
; #pragma unroll
;                     for (int hv = 0; hv < 2; ++hv) { const u32x2 c2 = half2(cur, hv), p2 = half2(pv, hv);
;                         const u32x2 q1 = dpp_prev<1>(p2, c2), q2 = dpp_prev<2>(p2, c2);
;                         float g0[4], g1[4], g2[4]; unpk4(c2, g0); unpk4(q1, g1); unpk4(q2, g2);
;                         const u32x2 r = finish2(g0, g1, g2, w0[hv], w1[hv], w2[hv], bb[hv], acc[ai][bj][m][hv], rs8[ai][m]);
;                         if (hv == 0) { hw.x = r.x; hw.y = r.y; } else { hw.z = r.x; hw.w = r.y; } }
;                     *(u32x4*)(H + (size_t)(R0 + fr + 16 * m) * 2816 + col8) = hw;
	v_pk_mul_f32 v[14:15], v[14:15], v[18:19]
	v_cvt_pk_bf16_f32 v18, v12, v13
	v_lshl_add_u64 v[12:13], v[174:175], 0, v[60:61]
	v_cvt_pk_bf16_f32 v19, v14, v15
	global_store_dwordx4 v[12:13], v[16:19], off sc1
	v_lshlrev_b32_e32 v12, 16, v1
	v_and_b32_e32 v13, 0xffff0000, v1
	v_mov_b32_dpp v17, v40 row_ror:2 row_mask:0xf bank_mask:0xf bound_ctrl:1
	v_and_b32_e32 v21, 0xffff0000, v36
	v_mov_b32_dpp v19, v41 row_ror:2 row_mask:0xf bank_mask:0xf bound_ctrl:1
	v_mov_b32_dpp v17, v36 row_shr:2 row_mask:0xf bank_mask:0xf
	v_lshlrev_b32_e32 v16, 16, v17
	v_and_b32_e32 v17, 0xffff0000, v17
	v_pk_fma_f32 v[16:17], v[84:85], v[16:17], v[96:97]
	v_mov_b32_dpp v15, v41 row_ror:1 row_mask:0xf bank_mask:0xf bound_ctrl:1
	v_pk_fma_f32 v[12:13], v[88:89], v[12:13], v[16:17]
	v_mov_b32_dpp v19, v37 row_shr:2 row_mask:0xf bank_mask:0xf
	v_pk_fma_f32 v[12:13], v[92:93], v[20:21], v[12:13]
	v_mov_b32_dpp v15, v37 row_shr:1 row_mask:0xf bank_mask:0xf
	v_pk_mul_f32 v[16:17], v[12:13], s[26:27] op_sel_hi:[1,0]
	v_lshlrev_b32_e32 v18, 16, v19
	v_med3_f32 v16, v16, s71, v224
	v_med3_f32 v17, v17, s71, v224
	v_pk_mul_f32 v[20:21], v[16:17], v[16:17]
	v_and_b32_e32 v19, 0xffff0000, v19
	v_pk_fma_f32 v[22:23], v[20:21], s[28:29], v[2:3] op_sel_hi:[1,0,0] neg_lo:[1,0,0] neg_hi:[1,0,0]
	v_pk_mul_f32 v[12:13], v[12:13], 0.5 op_sel_hi:[1,0]
	v_pk_fma_f32 v[22:23], v[20:21], v[22:23], s[34:35] op_sel_hi:[1,1,0]
	v_lshlrev_b32_e32 v14, 16, v15
	v_pk_fma_f32 v[22:23], v[20:21], v[22:23], s[36:37] op_sel_hi:[1,1,0]
	v_and_b32_e32 v15, 0xffff0000, v15
	v_pk_fma_f32 v[22:23], v[20:21], v[22:23], s[38:39] op_sel_hi:[1,1,0]
	v_mov_b32_dpp v1, v42 row_ror:1 row_mask:0xf bank_mask:0xf bound_ctrl:1
	v_pk_fma_f32 v[22:23], v[20:21], v[22:23], s[40:41] op_sel_hi:[1,1,0]
	s_nop 0
	v_pk_fma_f32 v[22:23], v[20:21], v[22:23], s[42:43] op_sel_hi:[1,1,0]
	v_mov_b32_dpp v1, v38 row_shr:1 row_mask:0xf bank_mask:0xf
	v_pk_fma_f32 v[20:21], v[20:21], v[22:23], s[44:45] op_sel_hi:[1,1,0]
	s_nop 0
	v_pk_mul_f32 v[16:17], v[16:17], v[20:21]
	s_nop 0
	v_pk_fma_f32 v[12:13], v[12:13], v[16:17], v[12:13]
	v_pk_fma_f32 v[16:17], v[86:87], v[18:19], v[98:99]
	v_pk_mul_f32 v[8:9], v[8:9], v[12:13]
	v_lshlrev_b32_e32 v12, 16, v37
	v_and_b32_e32 v13, 0xffff0000, v37
	v_pk_fma_f32 v[14:15], v[90:91], v[14:15], v[16:17]
	v_cvt_pk_bf16_f32 v8, v8, v9
	s_nop 0
	v_pk_fma_f32 v[12:13], v[94:95], v[12:13], v[14:15]
	s_nop 0
	v_pk_mul_f32 v[14:15], v[12:13], s[26:27] op_sel_hi:[1,0]
	v_pk_mul_f32 v[12:13], v[12:13], 0.5 op_sel_hi:[1,0]
	v_med3_f32 v14, v14, s71, v224
	v_med3_f32 v15, v15, s71, v224
	v_pk_mul_f32 v[16:17], v[14:15], v[14:15]
	s_nop 0
	v_pk_fma_f32 v[18:19], v[16:17], s[28:29], v[2:3] op_sel_hi:[1,0,0] neg_lo:[1,0,0] neg_hi:[1,0,0]
	s_nop 0
	v_pk_fma_f32 v[18:19], v[16:17], v[18:19], s[34:35] op_sel_hi:[1,1,0]
	s_nop 0
	v_pk_fma_f32 v[18:19], v[16:17], v[18:19], s[36:37] op_sel_hi:[1,1,0]
	s_nop 0
	v_pk_fma_f32 v[18:19], v[16:17], v[18:19], s[38:39] op_sel_hi:[1,1,0]
	s_nop 0
	v_pk_fma_f32 v[18:19], v[16:17], v[18:19], s[40:41] op_sel_hi:[1,1,0]
	s_nop 0
	v_pk_fma_f32 v[18:19], v[16:17], v[18:19], s[42:43] op_sel_hi:[1,1,0]
	s_nop 0
	v_pk_fma_f32 v[16:17], v[16:17], v[18:19], s[44:45] op_sel_hi:[1,1,0]
	v_lshlrev_b32_e32 v18, 16, v38
	v_pk_mul_f32 v[14:15], v[14:15], v[16:17]
	v_and_b32_e32 v19, 0xffff0000, v38
	v_pk_fma_f32 v[12:13], v[12:13], v[14:15], v[12:13]
	v_mov_b32_dpp v15, v42 row_ror:2 row_mask:0xf bank_mask:0xf bound_ctrl:1
	v_pk_mul_f32 v[10:11], v[10:11], v[12:13]
	v_mov_b32_dpp v17, v43 row_ror:2 row_mask:0xf bank_mask:0xf bound_ctrl:1
	v_mov_b32_dpp v15, v38 row_shr:2 row_mask:0xf bank_mask:0xf
	v_lshlrev_b32_e32 v14, 16, v15
	v_and_b32_e32 v15, 0xffff0000, v15
	v_cvt_pk_bf16_f32 v9, v10, v11
	v_lshlrev_b32_e32 v10, 16, v1
	v_and_b32_e32 v11, 0xffff0000, v1
	v_pk_fma_f32 v[14:15], v[64:65], v[14:15], v[80:81]
	v_mov_b32_dpp v13, v43 row_ror:1 row_mask:0xf bank_mask:0xf bound_ctrl:1
	v_pk_fma_f32 v[10:11], v[72:73], v[10:11], v[14:15]
	v_mov_b32_dpp v17, v39 row_shr:2 row_mask:0xf bank_mask:0xf
	v_pk_fma_f32 v[10:11], v[76:77], v[18:19], v[10:11]
	v_mov_b32_dpp v13, v39 row_shr:1 row_mask:0xf bank_mask:0xf
	v_pk_mul_f32 v[14:15], v[10:11], s[26:27] op_sel_hi:[1,0]
	v_lshlrev_b32_e32 v16, 16, v17
	v_med3_f32 v14, v14, s71, v224
	v_med3_f32 v15, v15, s71, v224
	v_pk_mul_f32 v[18:19], v[14:15], v[14:15]
	v_and_b32_e32 v17, 0xffff0000, v17
	v_pk_fma_f32 v[20:21], v[18:19], s[28:29], v[2:3] op_sel_hi:[1,0,0] neg_lo:[1,0,0] neg_hi:[1,0,0]
	v_pk_mul_f32 v[10:11], v[10:11], 0.5 op_sel_hi:[1,0]
	v_pk_fma_f32 v[20:21], v[18:19], v[20:21], s[34:35] op_sel_hi:[1,1,0]
	v_lshlrev_b32_e32 v12, 16, v13
	v_pk_fma_f32 v[20:21], v[18:19], v[20:21], s[36:37] op_sel_hi:[1,1,0]
	v_and_b32_e32 v13, 0xffff0000, v13
	v_pk_fma_f32 v[20:21], v[18:19], v[20:21], s[38:39] op_sel_hi:[1,1,0]
	s_nop 0
	v_pk_fma_f32 v[20:21], v[18:19], v[20:21], s[40:41] op_sel_hi:[1,1,0]
	s_nop 0
	v_pk_fma_f32 v[20:21], v[18:19], v[20:21], s[42:43] op_sel_hi:[1,1,0]
	s_nop 0
	v_pk_fma_f32 v[18:19], v[18:19], v[20:21], s[44:45] op_sel_hi:[1,1,0]
	s_nop 0
	v_pk_mul_f32 v[14:15], v[14:15], v[18:19]
	s_nop 0
	v_pk_fma_f32 v[10:11], v[10:11], v[14:15], v[10:11]
	v_pk_fma_f32 v[14:15], v[66:67], v[16:17], v[82:83]
	v_pk_mul_f32 v[4:5], v[4:5], v[10:11]
	v_lshlrev_b32_e32 v10, 16, v39
	v_and_b32_e32 v11, 0xffff0000, v39
	v_pk_fma_f32 v[12:13], v[74:75], v[12:13], v[14:15]
	s_nop 0
	v_pk_fma_f32 v[10:11], v[78:79], v[10:11], v[12:13]
	s_nop 0
	v_pk_mul_f32 v[12:13], v[10:11], s[26:27] op_sel_hi:[1,0]
	v_pk_mul_f32 v[10:11], v[10:11], 0.5 op_sel_hi:[1,0]
	v_med3_f32 v12, v12, s71, v224
	v_med3_f32 v13, v13, s71, v224
	v_pk_mul_f32 v[14:15], v[12:13], v[12:13]
	s_nop 0
	v_pk_fma_f32 v[2:3], v[14:15], s[28:29], v[2:3] op_sel_hi:[1,0,0] neg_lo:[1,0,0] neg_hi:[1,0,0]
	s_nop 0
	v_pk_fma_f32 v[2:3], v[14:15], v[2:3], s[34:35] op_sel_hi:[1,1,0]
	s_nop 0
	v_pk_fma_f32 v[2:3], v[14:15], v[2:3], s[36:37] op_sel_hi:[1,1,0]
	s_nop 0
	v_pk_fma_f32 v[2:3], v[14:15], v[2:3], s[38:39] op_sel_hi:[1,1,0]
	s_nop 0
	v_pk_fma_f32 v[2:3], v[14:15], v[2:3], s[40:41] op_sel_hi:[1,1,0]
	s_nop 0
	v_pk_fma_f32 v[2:3], v[14:15], v[2:3], s[42:43] op_sel_hi:[1,1,0]
	s_nop 0
	v_pk_fma_f32 v[2:3], v[14:15], v[2:3], s[44:45] op_sel_hi:[1,1,0]
	s_nop 0
	v_pk_mul_f32 v[2:3], v[12:13], v[2:3]
	s_nop 0
	v_pk_fma_f32 v[2:3], v[10:11], v[2:3], v[10:11]
	v_cvt_pk_bf16_f32 v10, v4, v5
	s_nop 0
	v_pk_mul_f32 v[2:3], v[6:7], v[2:3]
	s_nop 0
	v_cvt_pk_bf16_f32 v11, v2, v3
	v_lshl_add_u64 v[2:3], v[132:133], 0, v[60:61]
	global_store_dwordx4 v[2:3], v[8:11], off sc1
	s_andn2_b64 vcc, exec, s[50:51]
	s_mov_b64 s[0:1], -1
	s_cbranch_vccnz .LBB0_3124
